# v17: v14 plus all flat_* loads/stores/atomics rewritten as global_*
# speedup vs baseline: 1.0113x; 1.0113x over previous
.LBB0_8:
	s_or_b64 exec, exec, s[44:45]
	s_waitcnt vmcnt(0)
	ds_write2_b32 v46, v2, v3 offset1:1
	ds_write2_b32 v46, v4, v5 offset0:2 offset1:3
	v_add_u32_e32 v2, 0x420, v46
	ds_write2_b32 v2, v10, v11 offset1:1
	v_add_u32_e32 v2, 0x428, v46
	ds_write2_b32 v2, v12, v13 offset1:1
	v_add_u32_e32 v2, 0x840, v46
	ds_write2_b32 v2, v6, v7 offset1:1
	v_add_u32_e32 v2, 0x848, v46
	ds_write2_b32 v2, v8, v9 offset1:1
	v_add_u32_e32 v2, 0xc60, v46
	ds_write2_b32 v2, v18, v19 offset1:1
	v_add_u32_e32 v2, 0xc68, v46
	ds_write2_b32 v2, v20, v21 offset1:1
	v_add_u32_e32 v2, 0x1080, v46
	ds_write2_b32 v2, v14, v15 offset1:1
	v_add_u32_e32 v2, 0x1088, v46
	ds_write2_b32 v2, v16, v17 offset1:1
	v_add_u32_e32 v2, 0x14a0, v46
	ds_write2_b32 v2, v26, v27 offset1:1
	v_add_u32_e32 v2, 0x14a8, v46
	ds_write2_b32 v2, v28, v29 offset1:1
	v_add_u32_e32 v2, 0x18c0, v46
	ds_write2_b32 v2, v22, v23 offset1:1
	v_add_u32_e32 v2, 0x18c8, v46
	ds_write2_b32 v2, v24, v25 offset1:1
	v_add_u32_e32 v2, 0x1ce0, v46
	ds_write2_b32 v2, v30, v31 offset1:1
	v_add_u32_e32 v2, 0x1ce8, v46
	ds_write2_b32 v2, v32, v33 offset1:1
	s_waitcnt lgkmcnt(0)
	ds_read_b32 v2, v45
	ds_read_b32 v3, v45 offset:132
	ds_read_b32 v4, v45 offset:264
	ds_read_b32 v5, v45 offset:396
	ds_read_b32 v8, v45 offset:528
	ds_read_b32 v9, v45 offset:660
	ds_read_b32 v10, v45 offset:792
	ds_read_b32 v11, v45 offset:924
	s_waitcnt lgkmcnt(0)
	v_cvt_pk_bf16_f32 v2, v2, v3
	s_waitcnt lgkmcnt(4)
	v_cvt_pk_bf16_f32 v3, v4, v5
	s_waitcnt lgkmcnt(2)
	v_cvt_pk_bf16_f32 v4, v8, v9
	v_add_u32_e32 v8, s40, v43
	s_ashr_i32 s43, s42, 31
	v_ashrrev_i32_e32 v9, 31, v8
	v_lshl_add_u64 v[6:7], s[42:43], 1, v[38:39]
	s_waitcnt lgkmcnt(0)
	v_cvt_pk_bf16_f32 v5, v10, v11
	v_lshlrev_b64 v[10:11], 11, v[8:9]
	v_lshl_add_u64 v[10:11], v[6:7], 0, v[10:11]
	global_store_dwordx4 v[10:11], v[2:5], off
	ds_read_b32 v2, v45 offset:32
	ds_read_b32 v3, v45 offset:164
	ds_read_b32 v4, v45 offset:296
	ds_read_b32 v5, v45 offset:428
	ds_read_b32 v9, v45 offset:560
	ds_read_b32 v10, v45 offset:692
	ds_read_b32 v11, v45 offset:824
	ds_read_b32 v12, v45 offset:956
	s_waitcnt lgkmcnt(0)
	v_cvt_pk_bf16_f32 v2, v2, v3
	v_cvt_pk_bf16_f32 v3, v4, v5
	v_cvt_pk_bf16_f32 v4, v9, v10
	v_add_u32_e32 v10, 8, v8
	v_cvt_pk_bf16_f32 v5, v11, v12
	v_ashrrev_i32_e32 v11, 31, v10
	v_lshlrev_b64 v[10:11], 11, v[10:11]
	v_lshl_add_u64 v[10:11], v[6:7], 0, v[10:11]
	global_store_dwordx4 v[10:11], v[2:5], off
	ds_read_b32 v2, v45 offset:64
	ds_read_b32 v3, v45 offset:196
	ds_read_b32 v4, v45 offset:328
	ds_read_b32 v5, v45 offset:460
	ds_read_b32 v9, v45 offset:592
	ds_read_b32 v10, v45 offset:724
	ds_read_b32 v11, v45 offset:856
	ds_read_b32 v12, v45 offset:988
	s_waitcnt lgkmcnt(0)
	v_cvt_pk_bf16_f32 v2, v2, v3
	v_cvt_pk_bf16_f32 v3, v4, v5
	v_cvt_pk_bf16_f32 v4, v9, v10
	v_add_u32_e32 v10, 16, v8
	v_cvt_pk_bf16_f32 v5, v11, v12
	v_ashrrev_i32_e32 v11, 31, v10
	v_lshlrev_b64 v[10:11], 11, v[10:11]
	v_lshl_add_u64 v[10:11], v[6:7], 0, v[10:11]
	global_store_dwordx4 v[10:11], v[2:5], off
	ds_read_b32 v2, v45 offset:96
	ds_read_b32 v3, v45 offset:228
	ds_read_b32 v4, v45 offset:360
	ds_read_b32 v5, v45 offset:492
	ds_read_b32 v9, v45 offset:624
	ds_read_b32 v10, v45 offset:756
	ds_read_b32 v11, v45 offset:888
	ds_read_b32 v12, v45 offset:1020
	v_add_u32_e32 v8, 24, v8
	s_waitcnt lgkmcnt(0)
	v_cvt_pk_bf16_f32 v2, v2, v3
	v_cvt_pk_bf16_f32 v3, v4, v5
	v_cvt_pk_bf16_f32 v4, v9, v10
	v_ashrrev_i32_e32 v9, 31, v8
	v_lshlrev_b64 v[8:9], 11, v[8:9]
	v_cvt_pk_bf16_f32 v5, v11, v12
	v_lshl_add_u64 v[6:7], v[6:7], 0, v[8:9]
	global_store_dwordx4 v[6:7], v[2:5], off
	s_waitcnt lgkmcnt(0)
	s_add_i32 s47, s47, s33
	s_add_i32 s3, s3, s4
	s_cmpk_lt_i32 s47, 0x680
	s_cbranch_scc0 .LBB0_25

.LBB0_27:
	s_or_b64 exec, exec, s[44:45]
	s_waitcnt vmcnt(0)
	ds_write2_b32 v48, v2, v3 offset1:1
	ds_write2_b32 v48, v4, v5 offset0:2 offset1:3
	v_add_u32_e32 v2, 0x420, v48
	ds_write2_b32 v2, v10, v11 offset1:1
	v_add_u32_e32 v2, 0x428, v48
	ds_write2_b32 v2, v12, v13 offset1:1
	v_add_u32_e32 v2, 0x840, v48
	ds_write2_b32 v2, v6, v7 offset1:1
	v_add_u32_e32 v2, 0x848, v48
	ds_write2_b32 v2, v8, v9 offset1:1
	v_add_u32_e32 v2, 0xc60, v48
	ds_write2_b32 v2, v18, v19 offset1:1
	v_add_u32_e32 v2, 0xc68, v48
	ds_write2_b32 v2, v20, v21 offset1:1
	v_add_u32_e32 v2, 0x1080, v48
	ds_write2_b32 v2, v14, v15 offset1:1
	v_add_u32_e32 v2, 0x1088, v48
	ds_write2_b32 v2, v16, v17 offset1:1
	v_add_u32_e32 v2, 0x14a0, v48
	ds_write2_b32 v2, v26, v27 offset1:1
	v_add_u32_e32 v2, 0x14a8, v48
	ds_write2_b32 v2, v28, v29 offset1:1
	v_add_u32_e32 v2, 0x18c0, v48
	ds_write2_b32 v2, v22, v23 offset1:1
	v_add_u32_e32 v2, 0x18c8, v48
	ds_write2_b32 v2, v24, v25 offset1:1
	v_add_u32_e32 v2, 0x1ce0, v48
	ds_write2_b32 v2, v30, v31 offset1:1
	v_add_u32_e32 v2, 0x1ce8, v48
	ds_write2_b32 v2, v32, v33 offset1:1
	s_waitcnt lgkmcnt(0)
	ds_read_b32 v2, v47
	ds_read_b32 v3, v47 offset:132
	ds_read_b32 v4, v47 offset:264
	ds_read_b32 v5, v47 offset:396
	ds_read_b32 v8, v47 offset:528
	ds_read_b32 v9, v47 offset:660
	ds_read_b32 v10, v47 offset:792
	ds_read_b32 v11, v47 offset:924
	s_sub_i32 s0, 0, s1
	s_add_i32 s0, s0, s3
	s_waitcnt lgkmcnt(0)
	v_cvt_pk_bf16_f32 v2, v2, v3
	v_cvt_pk_bf16_f32 v3, v4, v5
	v_cvt_pk_bf16_f32 v4, v8, v9
	v_add_u32_e32 v8, s0, v46
	s_ashr_i32 s29, s28, 31
	v_ashrrev_i32_e32 v9, 31, v8
	v_lshl_add_u64 v[6:7], s[28:29], 1, v[38:39]
	v_cvt_pk_bf16_f32 v5, v10, v11
	v_lshlrev_b64 v[10:11], 11, v[8:9]
	v_lshl_add_u64 v[10:11], v[6:7], 0, v[10:11]
	global_store_dwordx4 v[10:11], v[2:5], off
	ds_read_b32 v2, v47 offset:32
	ds_read_b32 v3, v47 offset:164
	ds_read_b32 v4, v47 offset:296
	ds_read_b32 v5, v47 offset:428
	ds_read_b32 v9, v47 offset:560
	ds_read_b32 v10, v47 offset:692
	ds_read_b32 v11, v47 offset:824
	ds_read_b32 v12, v47 offset:956
	s_waitcnt lgkmcnt(0)
	v_cvt_pk_bf16_f32 v2, v2, v3
	v_cvt_pk_bf16_f32 v3, v4, v5
	v_cvt_pk_bf16_f32 v4, v9, v10
	v_add_u32_e32 v10, 8, v8
	v_cvt_pk_bf16_f32 v5, v11, v12
	v_ashrrev_i32_e32 v11, 31, v10
	v_lshlrev_b64 v[10:11], 11, v[10:11]
	v_lshl_add_u64 v[10:11], v[6:7], 0, v[10:11]
	global_store_dwordx4 v[10:11], v[2:5], off
	ds_read_b32 v2, v47 offset:64
	ds_read_b32 v3, v47 offset:196
	ds_read_b32 v4, v47 offset:328
	ds_read_b32 v5, v47 offset:460
	ds_read_b32 v9, v47 offset:592
	ds_read_b32 v10, v47 offset:724
	ds_read_b32 v11, v47 offset:856
	ds_read_b32 v12, v47 offset:988
	s_waitcnt lgkmcnt(0)
	v_cvt_pk_bf16_f32 v2, v2, v3
	v_cvt_pk_bf16_f32 v3, v4, v5
	v_cvt_pk_bf16_f32 v4, v9, v10
	v_add_u32_e32 v10, 16, v8
	v_cvt_pk_bf16_f32 v5, v11, v12
	v_ashrrev_i32_e32 v11, 31, v10
	v_lshlrev_b64 v[10:11], 11, v[10:11]
	v_lshl_add_u64 v[10:11], v[6:7], 0, v[10:11]
	global_store_dwordx4 v[10:11], v[2:5], off
	ds_read_b32 v2, v47 offset:96
	ds_read_b32 v3, v47 offset:228
	ds_read_b32 v4, v47 offset:360
	ds_read_b32 v5, v47 offset:492
	ds_read_b32 v9, v47 offset:624
	ds_read_b32 v10, v47 offset:756
	ds_read_b32 v11, v47 offset:888
	ds_read_b32 v12, v47 offset:1020
	v_add_u32_e32 v8, 24, v8
	s_waitcnt lgkmcnt(0)
	v_cvt_pk_bf16_f32 v2, v2, v3
	v_cvt_pk_bf16_f32 v3, v4, v5
	v_cvt_pk_bf16_f32 v4, v9, v10
	v_ashrrev_i32_e32 v9, 31, v8
	v_lshlrev_b64 v[8:9], 11, v[8:9]
	v_cvt_pk_bf16_f32 v5, v11, v12
	v_lshl_add_u64 v[6:7], v[6:7], 0, v[8:9]
	global_store_dwordx4 v[6:7], v[2:5], off
	s_waitcnt lgkmcnt(0)
	s_add_i32 s46, s46, s33
	s_add_i32 s3, s3, s4
	s_cmpk_lt_i32 s46, 0x200
	s_cbranch_scc0 .LBB0_44

.LBB0_46:
	s_or_b64 exec, exec, s[30:31]
	s_waitcnt vmcnt(0)
	ds_write2_b32 v46, v2, v3 offset1:1
	ds_write2_b32 v46, v4, v5 offset0:2 offset1:3
	v_add_u32_e32 v2, 0x420, v46
	ds_write2_b32 v2, v10, v11 offset1:1
	v_add_u32_e32 v2, 0x428, v46
	ds_write2_b32 v2, v12, v13 offset1:1
	v_add_u32_e32 v2, 0x840, v46
	ds_write2_b32 v2, v6, v7 offset1:1
	v_add_u32_e32 v2, 0x848, v46
	ds_write2_b32 v2, v8, v9 offset1:1
	v_add_u32_e32 v2, 0xc60, v46
	ds_write2_b32 v2, v18, v19 offset1:1
	v_add_u32_e32 v2, 0xc68, v46
	ds_write2_b32 v2, v20, v21 offset1:1
	v_add_u32_e32 v2, 0x1080, v46
	ds_write2_b32 v2, v14, v15 offset1:1
	v_add_u32_e32 v2, 0x1088, v46
	ds_write2_b32 v2, v16, v17 offset1:1
	v_add_u32_e32 v2, 0x14a0, v46
	ds_write2_b32 v2, v26, v27 offset1:1
	v_add_u32_e32 v2, 0x14a8, v46
	ds_write2_b32 v2, v28, v29 offset1:1
	v_add_u32_e32 v2, 0x18c0, v46
	ds_write2_b32 v2, v22, v23 offset1:1
	v_add_u32_e32 v2, 0x18c8, v46
	ds_write2_b32 v2, v24, v25 offset1:1
	v_add_u32_e32 v2, 0x1ce0, v46
	ds_write2_b32 v2, v30, v31 offset1:1
	v_add_u32_e32 v2, 0x1ce8, v46
	ds_write2_b32 v2, v32, v33 offset1:1
	s_waitcnt lgkmcnt(0)
	ds_read_b32 v2, v45
	ds_read_b32 v3, v45 offset:132
	ds_read_b32 v4, v45 offset:264
	ds_read_b32 v5, v45 offset:396
	ds_read_b32 v8, v45 offset:528
	ds_read_b32 v9, v45 offset:660
	ds_read_b32 v10, v45 offset:792
	ds_read_b32 v11, v45 offset:924
	s_waitcnt lgkmcnt(0)
	v_cvt_pk_bf16_f32 v2, v2, v3
	v_cvt_pk_bf16_f32 v3, v4, v5
	v_cvt_pk_bf16_f32 v4, v8, v9
	v_add_u32_e32 v8, s6, v43
	s_ashr_i32 s29, s28, 31
	v_ashrrev_i32_e32 v9, 31, v8
	v_lshl_add_u64 v[6:7], s[28:29], 1, v[38:39]
	v_cvt_pk_bf16_f32 v5, v10, v11
	v_lshlrev_b64 v[10:11], 11, v[8:9]
	v_lshl_add_u64 v[10:11], v[6:7], 0, v[10:11]
	global_store_dwordx4 v[10:11], v[2:5], off
	ds_read_b32 v2, v45 offset:32
	ds_read_b32 v3, v45 offset:164
	ds_read_b32 v4, v45 offset:296
	ds_read_b32 v5, v45 offset:428
	ds_read_b32 v9, v45 offset:560
	ds_read_b32 v10, v45 offset:692
	ds_read_b32 v11, v45 offset:824
	ds_read_b32 v12, v45 offset:956
	s_waitcnt lgkmcnt(0)
	v_cvt_pk_bf16_f32 v2, v2, v3
	v_cvt_pk_bf16_f32 v3, v4, v5
	v_cvt_pk_bf16_f32 v4, v9, v10
	v_add_u32_e32 v10, 8, v8
	v_cvt_pk_bf16_f32 v5, v11, v12
	v_ashrrev_i32_e32 v11, 31, v10
	v_lshlrev_b64 v[10:11], 11, v[10:11]
	v_lshl_add_u64 v[10:11], v[6:7], 0, v[10:11]
	global_store_dwordx4 v[10:11], v[2:5], off
	ds_read_b32 v2, v45 offset:64
	ds_read_b32 v3, v45 offset:196
	ds_read_b32 v4, v45 offset:328
	ds_read_b32 v5, v45 offset:460
	ds_read_b32 v9, v45 offset:592
	ds_read_b32 v10, v45 offset:724
	ds_read_b32 v11, v45 offset:856
	ds_read_b32 v12, v45 offset:988
	s_waitcnt lgkmcnt(0)
	v_cvt_pk_bf16_f32 v2, v2, v3
	v_cvt_pk_bf16_f32 v3, v4, v5
	v_cvt_pk_bf16_f32 v4, v9, v10
	v_add_u32_e32 v10, 16, v8
	v_cvt_pk_bf16_f32 v5, v11, v12
	v_ashrrev_i32_e32 v11, 31, v10
	v_lshlrev_b64 v[10:11], 11, v[10:11]
	v_lshl_add_u64 v[10:11], v[6:7], 0, v[10:11]
	global_store_dwordx4 v[10:11], v[2:5], off
	ds_read_b32 v2, v45 offset:96
	ds_read_b32 v3, v45 offset:228
	ds_read_b32 v4, v45 offset:360
	ds_read_b32 v5, v45 offset:492
	ds_read_b32 v9, v45 offset:624
	ds_read_b32 v10, v45 offset:756
	ds_read_b32 v11, v45 offset:888
	ds_read_b32 v12, v45 offset:1020
	v_add_u32_e32 v8, 24, v8
	s_waitcnt lgkmcnt(0)
	v_cvt_pk_bf16_f32 v2, v2, v3
	v_cvt_pk_bf16_f32 v3, v4, v5
	v_cvt_pk_bf16_f32 v4, v9, v10
	v_ashrrev_i32_e32 v9, 31, v8
	v_lshlrev_b64 v[8:9], 11, v[8:9]
	v_cvt_pk_bf16_f32 v5, v11, v12
	v_lshl_add_u64 v[6:7], v[6:7], 0, v[8:9]
	global_store_dwordx4 v[6:7], v[2:5], off
	s_waitcnt lgkmcnt(0)
	s_add_i32 s45, s45, s33
	s_add_i32 s3, s3, s4
	s_cmpk_lt_i32 s45, 0x680
	s_cbranch_scc0 .LBB0_63

.LBB0_65:
	s_or_b64 exec, exec, s[28:29]
	s_waitcnt vmcnt(0)
	ds_write2_b32 v48, v2, v3 offset1:1
	ds_write2_b32 v48, v4, v5 offset0:2 offset1:3
	v_add_u32_e32 v2, 0x420, v48
	ds_write2_b32 v2, v10, v11 offset1:1
	v_add_u32_e32 v2, 0x428, v48
	ds_write2_b32 v2, v12, v13 offset1:1
	v_add_u32_e32 v2, 0x840, v48
	ds_write2_b32 v2, v6, v7 offset1:1
	v_add_u32_e32 v2, 0x848, v48
	ds_write2_b32 v2, v8, v9 offset1:1
	v_add_u32_e32 v2, 0xc60, v48
	ds_write2_b32 v2, v18, v19 offset1:1
	v_add_u32_e32 v2, 0xc68, v48
	ds_write2_b32 v2, v20, v21 offset1:1
	v_add_u32_e32 v2, 0x1080, v48
	ds_write2_b32 v2, v14, v15 offset1:1
	v_add_u32_e32 v2, 0x1088, v48
	ds_write2_b32 v2, v16, v17 offset1:1
	v_add_u32_e32 v2, 0x14a0, v48
	ds_write2_b32 v2, v26, v27 offset1:1
	v_add_u32_e32 v2, 0x14a8, v48
	ds_write2_b32 v2, v28, v29 offset1:1
	v_add_u32_e32 v2, 0x18c0, v48
	ds_write2_b32 v2, v22, v23 offset1:1
	v_add_u32_e32 v2, 0x18c8, v48
	ds_write2_b32 v2, v24, v25 offset1:1
	v_add_u32_e32 v2, 0x1ce0, v48
	ds_write2_b32 v2, v30, v31 offset1:1
	v_add_u32_e32 v2, 0x1ce8, v48
	ds_write2_b32 v2, v32, v33 offset1:1
	s_waitcnt lgkmcnt(0)
	ds_read_b32 v2, v47
	ds_read_b32 v3, v47 offset:132
	ds_read_b32 v4, v47 offset:264
	ds_read_b32 v5, v47 offset:396
	ds_read_b32 v8, v47 offset:528
	ds_read_b32 v9, v47 offset:660
	ds_read_b32 v10, v47 offset:792
	ds_read_b32 v11, v47 offset:924
	s_sub_i32 s0, 0, s1
	s_add_i32 s0, s0, s3
	s_waitcnt lgkmcnt(0)
	v_cvt_pk_bf16_f32 v2, v2, v3
	v_cvt_pk_bf16_f32 v3, v4, v5
	v_cvt_pk_bf16_f32 v4, v8, v9
	v_add_u32_e32 v8, s0, v46
	s_ashr_i32 s25, s24, 31
	v_ashrrev_i32_e32 v9, 31, v8
	v_lshl_add_u64 v[6:7], s[24:25], 1, v[38:39]
	v_cvt_pk_bf16_f32 v5, v10, v11
	v_lshlrev_b64 v[10:11], 11, v[8:9]
	v_lshl_add_u64 v[10:11], v[6:7], 0, v[10:11]
	global_store_dwordx4 v[10:11], v[2:5], off
	ds_read_b32 v2, v47 offset:32
	ds_read_b32 v3, v47 offset:164
	ds_read_b32 v4, v47 offset:296
	ds_read_b32 v5, v47 offset:428
	ds_read_b32 v9, v47 offset:560
	ds_read_b32 v10, v47 offset:692
	ds_read_b32 v11, v47 offset:824
	ds_read_b32 v12, v47 offset:956
	s_waitcnt lgkmcnt(0)
	v_cvt_pk_bf16_f32 v2, v2, v3
	v_cvt_pk_bf16_f32 v3, v4, v5
	v_cvt_pk_bf16_f32 v4, v9, v10
	v_add_u32_e32 v10, 8, v8
	v_cvt_pk_bf16_f32 v5, v11, v12
	v_ashrrev_i32_e32 v11, 31, v10
	v_lshlrev_b64 v[10:11], 11, v[10:11]
	v_lshl_add_u64 v[10:11], v[6:7], 0, v[10:11]
	global_store_dwordx4 v[10:11], v[2:5], off
	ds_read_b32 v2, v47 offset:64
	ds_read_b32 v3, v47 offset:196
	ds_read_b32 v4, v47 offset:328
	ds_read_b32 v5, v47 offset:460
	ds_read_b32 v9, v47 offset:592
	ds_read_b32 v10, v47 offset:724
	ds_read_b32 v11, v47 offset:856
	ds_read_b32 v12, v47 offset:988
	s_waitcnt lgkmcnt(0)
	v_cvt_pk_bf16_f32 v2, v2, v3
	v_cvt_pk_bf16_f32 v3, v4, v5
	v_cvt_pk_bf16_f32 v4, v9, v10
	v_add_u32_e32 v10, 16, v8
	v_cvt_pk_bf16_f32 v5, v11, v12
	v_ashrrev_i32_e32 v11, 31, v10
	v_lshlrev_b64 v[10:11], 11, v[10:11]
	v_lshl_add_u64 v[10:11], v[6:7], 0, v[10:11]
	global_store_dwordx4 v[10:11], v[2:5], off
	ds_read_b32 v2, v47 offset:96
	ds_read_b32 v3, v47 offset:228
	ds_read_b32 v4, v47 offset:360
	ds_read_b32 v5, v47 offset:492
	ds_read_b32 v9, v47 offset:624
	ds_read_b32 v10, v47 offset:756
	ds_read_b32 v11, v47 offset:888
	ds_read_b32 v12, v47 offset:1020
	v_add_u32_e32 v8, 24, v8
	s_waitcnt lgkmcnt(0)
	v_cvt_pk_bf16_f32 v2, v2, v3
	v_cvt_pk_bf16_f32 v3, v4, v5
	v_cvt_pk_bf16_f32 v4, v9, v10
	v_ashrrev_i32_e32 v9, 31, v8
	v_lshlrev_b64 v[8:9], 11, v[8:9]
	v_cvt_pk_bf16_f32 v5, v11, v12
	v_lshl_add_u64 v[6:7], v[6:7], 0, v[8:9]
	global_store_dwordx4 v[6:7], v[2:5], off
	s_waitcnt lgkmcnt(0)
	s_add_i32 s30, s30, s33
	s_add_i32 s3, s3, s4
	s_cmpk_lt_i32 s30, 0x200
	s_cbranch_scc0 .LBB0_82

.LBB0_84:
	s_or_b64 exec, exec, s[26:27]
	s_waitcnt vmcnt(0)
	ds_write2_b32 v48, v2, v3 offset1:1
	ds_write2_b32 v48, v4, v5 offset0:2 offset1:3
	v_add_u32_e32 v2, 0x420, v48
	ds_write2_b32 v2, v10, v11 offset1:1
	v_add_u32_e32 v2, 0x428, v48
	ds_write2_b32 v2, v12, v13 offset1:1
	v_add_u32_e32 v2, 0x840, v48
	ds_write2_b32 v2, v6, v7 offset1:1
	v_add_u32_e32 v2, 0x848, v48
	ds_write2_b32 v2, v8, v9 offset1:1
	v_add_u32_e32 v2, 0xc60, v48
	ds_write2_b32 v2, v18, v19 offset1:1
	v_add_u32_e32 v2, 0xc68, v48
	ds_write2_b32 v2, v20, v21 offset1:1
	v_add_u32_e32 v2, 0x1080, v48
	ds_write2_b32 v2, v14, v15 offset1:1
	v_add_u32_e32 v2, 0x1088, v48
	ds_write2_b32 v2, v16, v17 offset1:1
	v_add_u32_e32 v2, 0x14a0, v48
	ds_write2_b32 v2, v26, v27 offset1:1
	v_add_u32_e32 v2, 0x14a8, v48
	ds_write2_b32 v2, v28, v29 offset1:1
	v_add_u32_e32 v2, 0x18c0, v48
	ds_write2_b32 v2, v22, v23 offset1:1
	v_add_u32_e32 v2, 0x18c8, v48
	ds_write2_b32 v2, v24, v25 offset1:1
	v_add_u32_e32 v2, 0x1ce0, v48
	ds_write2_b32 v2, v30, v31 offset1:1
	v_add_u32_e32 v2, 0x1ce8, v48
	ds_write2_b32 v2, v32, v33 offset1:1
	s_waitcnt lgkmcnt(0)
	ds_read_b32 v2, v47
	ds_read_b32 v3, v47 offset:132
	ds_read_b32 v4, v47 offset:264
	ds_read_b32 v5, v47 offset:396
	ds_read_b32 v8, v47 offset:528
	ds_read_b32 v9, v47 offset:660
	ds_read_b32 v10, v47 offset:792
	ds_read_b32 v11, v47 offset:924
	s_sub_i32 s0, 0, s1
	s_add_i32 s0, s0, s3
	s_waitcnt lgkmcnt(0)
	v_cvt_pk_bf16_f32 v2, v2, v3
	v_cvt_pk_bf16_f32 v3, v4, v5
	v_cvt_pk_bf16_f32 v4, v8, v9
	v_add_u32_e32 v8, s0, v46
	s_ashr_i32 s25, s24, 31
	v_ashrrev_i32_e32 v9, 31, v8
	v_lshl_add_u64 v[6:7], s[24:25], 1, v[38:39]
	v_cvt_pk_bf16_f32 v5, v10, v11
	v_lshlrev_b64 v[10:11], 11, v[8:9]
	v_lshl_add_u64 v[10:11], v[6:7], 0, v[10:11]
	global_store_dwordx4 v[10:11], v[2:5], off
	ds_read_b32 v2, v47 offset:32
	ds_read_b32 v3, v47 offset:164
	ds_read_b32 v4, v47 offset:296
	ds_read_b32 v5, v47 offset:428
	ds_read_b32 v9, v47 offset:560
	ds_read_b32 v10, v47 offset:692
	ds_read_b32 v11, v47 offset:824
	ds_read_b32 v12, v47 offset:956
	s_waitcnt lgkmcnt(0)
	v_cvt_pk_bf16_f32 v2, v2, v3
	v_cvt_pk_bf16_f32 v3, v4, v5
	v_cvt_pk_bf16_f32 v4, v9, v10
	v_add_u32_e32 v10, 8, v8
	v_cvt_pk_bf16_f32 v5, v11, v12
	v_ashrrev_i32_e32 v11, 31, v10
	v_lshlrev_b64 v[10:11], 11, v[10:11]
	v_lshl_add_u64 v[10:11], v[6:7], 0, v[10:11]
	global_store_dwordx4 v[10:11], v[2:5], off
	ds_read_b32 v2, v47 offset:64
	ds_read_b32 v3, v47 offset:196
	ds_read_b32 v4, v47 offset:328
	ds_read_b32 v5, v47 offset:460
	ds_read_b32 v9, v47 offset:592
	ds_read_b32 v10, v47 offset:724
	ds_read_b32 v11, v47 offset:856
	ds_read_b32 v12, v47 offset:988
	s_waitcnt lgkmcnt(0)
	v_cvt_pk_bf16_f32 v2, v2, v3
	v_cvt_pk_bf16_f32 v3, v4, v5
	v_cvt_pk_bf16_f32 v4, v9, v10
	v_add_u32_e32 v10, 16, v8
	v_cvt_pk_bf16_f32 v5, v11, v12
	v_ashrrev_i32_e32 v11, 31, v10
	v_lshlrev_b64 v[10:11], 11, v[10:11]
	v_lshl_add_u64 v[10:11], v[6:7], 0, v[10:11]
	global_store_dwordx4 v[10:11], v[2:5], off
	ds_read_b32 v2, v47 offset:96
	ds_read_b32 v3, v47 offset:228
	ds_read_b32 v4, v47 offset:360
	ds_read_b32 v5, v47 offset:492
	ds_read_b32 v9, v47 offset:624
	ds_read_b32 v10, v47 offset:756
	ds_read_b32 v11, v47 offset:888
	ds_read_b32 v12, v47 offset:1020
	v_add_u32_e32 v8, 24, v8
	s_waitcnt lgkmcnt(0)
	v_cvt_pk_bf16_f32 v2, v2, v3
	v_cvt_pk_bf16_f32 v3, v4, v5
	v_cvt_pk_bf16_f32 v4, v9, v10
	v_ashrrev_i32_e32 v9, 31, v8
	v_lshlrev_b64 v[8:9], 11, v[8:9]
	v_cvt_pk_bf16_f32 v5, v11, v12
	v_lshl_add_u64 v[6:7], v[6:7], 0, v[8:9]
	global_store_dwordx4 v[6:7], v[2:5], off
	s_waitcnt lgkmcnt(0)
	s_add_i32 s28, s28, s33
	s_add_i32 s3, s3, s4
	s_cmpk_lt_i32 s28, 0x400
	s_cbranch_scc0 .LBB0_101

.LBB0_105:
	s_or_b64 exec, exec, s[24:25]
	s_waitcnt vmcnt(0)
	ds_write2_b32 v54, v2, v3 offset1:1
	ds_write2_b32 v54, v4, v5 offset0:2 offset1:3
	v_add_u32_e32 v2, 0x420, v54
	ds_write2_b32 v2, v10, v11 offset1:1
	v_add_u32_e32 v2, 0x428, v54
	ds_write2_b32 v2, v12, v13 offset1:1
	v_add_u32_e32 v2, 0x840, v54
	ds_write2_b32 v2, v6, v7 offset1:1
	v_add_u32_e32 v2, 0x848, v54
	ds_write2_b32 v2, v8, v9 offset1:1
	v_add_u32_e32 v2, 0xc60, v54
	ds_write2_b32 v2, v18, v19 offset1:1
	v_add_u32_e32 v2, 0xc68, v54
	ds_write2_b32 v2, v20, v21 offset1:1
	v_add_u32_e32 v2, 0x1080, v54
	ds_write2_b32 v2, v14, v15 offset1:1
	v_add_u32_e32 v2, 0x1088, v54
	ds_write2_b32 v2, v16, v17 offset1:1
	v_add_u32_e32 v2, 0x14a0, v54
	ds_write2_b32 v2, v26, v27 offset1:1
	v_add_u32_e32 v2, 0x14a8, v54
	ds_write2_b32 v2, v28, v29 offset1:1
	v_add_u32_e32 v2, 0x18c0, v54
	ds_write2_b32 v2, v22, v23 offset1:1
	v_add_u32_e32 v2, 0x18c8, v54
	ds_write2_b32 v2, v24, v25 offset1:1
	v_add_u32_e32 v2, 0x1ce0, v54
	ds_write2_b32 v2, v30, v31 offset1:1
	v_add_u32_e32 v2, 0x1ce8, v54
	ds_write2_b32 v2, v32, v33 offset1:1
	s_waitcnt lgkmcnt(0)
	ds_read_b32 v2, v52
	ds_read_b32 v3, v52 offset:132
	ds_read_b32 v4, v52 offset:264
	ds_read_b32 v5, v52 offset:396
	ds_read_b32 v8, v52 offset:528
	ds_read_b32 v9, v52 offset:660
	ds_read_b32 v10, v52 offset:792
	ds_read_b32 v11, v52 offset:924
	s_sub_i32 s0, 0, s1
	s_add_i32 s0, s0, s3
	s_waitcnt lgkmcnt(0)
	v_cvt_pk_bf16_f32 v2, v2, v3
	v_cvt_pk_bf16_f32 v3, v4, v5
	v_cvt_pk_bf16_f32 v4, v8, v9
	v_add_u32_e32 v8, s0, v35
	s_ashr_i32 s9, s8, 31
	v_ashrrev_i32_e32 v9, 31, v8
	v_lshl_add_u64 v[6:7], s[8:9], 1, v[42:43]
	v_cvt_pk_bf16_f32 v5, v10, v11
	v_lshlrev_b64 v[10:11], 11, v[8:9]
	v_lshl_add_u64 v[10:11], v[6:7], 0, v[10:11]
	global_store_dwordx4 v[10:11], v[2:5], off
	ds_read_b32 v2, v52 offset:32
	ds_read_b32 v3, v52 offset:164
	ds_read_b32 v4, v52 offset:296
	ds_read_b32 v5, v52 offset:428
	ds_read_b32 v9, v52 offset:560
	ds_read_b32 v10, v52 offset:692
	ds_read_b32 v11, v52 offset:824
	ds_read_b32 v12, v52 offset:956
	s_waitcnt lgkmcnt(0)
	v_cvt_pk_bf16_f32 v2, v2, v3
	v_cvt_pk_bf16_f32 v3, v4, v5
	v_cvt_pk_bf16_f32 v4, v9, v10
	v_add_u32_e32 v10, 8, v8
	v_cvt_pk_bf16_f32 v5, v11, v12
	v_ashrrev_i32_e32 v11, 31, v10
	v_lshlrev_b64 v[10:11], 11, v[10:11]
	v_lshl_add_u64 v[10:11], v[6:7], 0, v[10:11]
	global_store_dwordx4 v[10:11], v[2:5], off
	ds_read_b32 v2, v52 offset:64
	ds_read_b32 v3, v52 offset:196
	ds_read_b32 v4, v52 offset:328
	ds_read_b32 v5, v52 offset:460
	ds_read_b32 v9, v52 offset:592
	ds_read_b32 v10, v52 offset:724
	ds_read_b32 v11, v52 offset:856
	ds_read_b32 v12, v52 offset:988
	s_waitcnt lgkmcnt(0)
	v_cvt_pk_bf16_f32 v2, v2, v3
	v_cvt_pk_bf16_f32 v3, v4, v5
	v_cvt_pk_bf16_f32 v4, v9, v10
	v_add_u32_e32 v10, 16, v8
	v_cvt_pk_bf16_f32 v5, v11, v12
	v_ashrrev_i32_e32 v11, 31, v10
	v_lshlrev_b64 v[10:11], 11, v[10:11]
	v_lshl_add_u64 v[10:11], v[6:7], 0, v[10:11]
	global_store_dwordx4 v[10:11], v[2:5], off
	ds_read_b32 v2, v52 offset:96
	ds_read_b32 v3, v52 offset:228
	ds_read_b32 v4, v52 offset:360
	ds_read_b32 v5, v52 offset:492
	ds_read_b32 v9, v52 offset:624
	ds_read_b32 v10, v52 offset:756
	ds_read_b32 v11, v52 offset:888
	ds_read_b32 v12, v52 offset:1020
	v_add_u32_e32 v8, 24, v8
	s_waitcnt lgkmcnt(0)
	v_cvt_pk_bf16_f32 v2, v2, v3
	v_cvt_pk_bf16_f32 v3, v4, v5
	v_cvt_pk_bf16_f32 v4, v9, v10
	v_ashrrev_i32_e32 v9, 31, v8
	v_lshlrev_b64 v[8:9], 11, v[8:9]
	v_cvt_pk_bf16_f32 v5, v11, v12
	v_lshl_add_u64 v[6:7], v[6:7], 0, v[8:9]
	global_store_dwordx4 v[6:7], v[2:5], off
	s_waitcnt lgkmcnt(0)
	s_add_i32 s26, s26, s33
	s_add_i32 s3, s3, s4
	s_cmpk_lt_i32 s26, 0x200
	s_cbranch_scc0 .LBB0_122

.LBB0_127:
	s_ashr_i32 s0, s1, 31
	s_lshr_b32 s0, s0, 29
	s_add_i32 s0, s1, s0
	s_ashr_i32 s0, s0, 3
	s_lshl_b32 s26, s0, 6
	s_lshl_b32 s24, s0, 8
	v_or_b32_e32 v14, s26, v52
	s_sub_i32 s24, s41, s24
	v_or_b32_e32 v16, 8, v14
	v_or_b32_e32 v18, 16, v14
	v_or_b32_e32 v20, 24, v14
	v_or_b32_e32 v22, 32, v14
	v_or_b32_e32 v24, 40, v14
	v_or_b32_e32 v26, 48, v14
	v_or_b32_e32 v28, 56, v14
	s_ashr_i32 s25, s24, 31
	v_ashrrev_i32_e32 v15, 31, v14
	v_ashrrev_i32_e32 v17, 31, v16
	v_ashrrev_i32_e32 v19, 31, v18
	v_ashrrev_i32_e32 v21, 31, v20
	v_ashrrev_i32_e32 v23, 31, v22
	v_ashrrev_i32_e32 v25, 31, v24
	v_ashrrev_i32_e32 v27, 31, v26
	v_ashrrev_i32_e32 v29, 31, v28
	v_lshl_add_u64 v[30:31], s[24:25], 2, v[4:5]
	v_lshlrev_b64 v[14:15], 10, v[14:15]
	v_lshlrev_b64 v[32:33], 10, v[16:17]
	v_lshlrev_b64 v[18:19], 10, v[18:19]
	v_lshlrev_b64 v[20:21], 10, v[20:21]
	v_lshlrev_b64 v[22:23], 10, v[22:23]
	v_lshlrev_b64 v[24:25], 10, v[24:25]
	v_lshlrev_b64 v[26:27], 10, v[26:27]
	v_lshlrev_b64 v[28:29], 10, v[28:29]
	v_lshl_add_u64 v[14:15], v[30:31], 0, v[14:15]
	v_lshl_add_u64 v[32:33], v[30:31], 0, v[32:33]
	v_lshl_add_u64 v[42:43], v[30:31], 0, v[18:19]
	v_lshl_add_u64 v[44:45], v[30:31], 0, v[20:21]
	v_lshl_add_u64 v[46:47], v[30:31], 0, v[22:23]
	v_lshl_add_u64 v[48:49], v[30:31], 0, v[24:25]
	v_lshl_add_u64 v[62:63], v[30:31], 0, v[26:27]
	v_lshl_add_u64 v[64:65], v[30:31], 0, v[28:29]
	global_load_dwordx4 v[14:17], v[14:15], off nt
	s_nop 0
	global_load_dwordx4 v[18:21], v[32:33], off nt
	global_load_dwordx4 v[22:25], v[42:43], off nt
	global_load_dwordx4 v[26:29], v[44:45], off nt
	s_nop 0
	global_load_dwordx4 v[30:33], v[46:47], off nt
	global_load_dwordx4 v[42:45], v[48:49], off nt
	s_nop 0
	global_load_dwordx4 v[46:49], v[62:63], off nt
	s_nop 0
	global_load_dwordx4 v[62:65], v[64:65], off nt
	s_lshl_b32 s0, s0, 9
	s_sub_i32 s0, s40, s0
	s_and_b32 s0, s0, 0xffffff00
	s_and_b32 s24, s24, 0x60
	s_add_i32 s0, s0, s31
	s_or_b32 s0, s24, s0
	v_or_b32_e32 v68, s0, v52
	s_ashr_i32 s27, s26, 31
	v_ashrrev_i32_e32 v69, 31, v68
	v_lshl_add_u64 v[66:67], s[26:27], 1, v[2:3]
	v_lshlrev_b64 v[68:69], 9, v[68:69]
	v_lshl_add_u64 v[68:69], v[66:67], 0, v[68:69]
	v_or_b32_e32 v70, s0, v1
	v_ashrrev_i32_e32 v71, 31, v70
	v_lshlrev_b64 v[70:71], 9, v[70:71]
	v_lshl_add_u64 v[70:71], v[66:67], 0, v[70:71]
	v_or_b32_e32 v72, s0, v50
	v_ashrrev_i32_e32 v73, 31, v72
	v_lshlrev_b64 v[72:73], 9, v[72:73]
	v_lshl_add_u64 v[72:73], v[66:67], 0, v[72:73]
	v_or_b32_e32 v74, s0, v51
	v_ashrrev_i32_e32 v75, 31, v74
	v_lshlrev_b64 v[74:75], 9, v[74:75]
	s_add_i32 s1, s1, s33
	s_add_i32 s41, s41, s3
	s_add_i32 s40, s40, s30
	s_cmp_lt_i32 s1, 32
	s_waitcnt vmcnt(0)
	ds_write2_b32 v57, v14, v15 offset1:1
	ds_write2_b32 v57, v16, v17 offset0:2 offset1:3
	ds_write2_b32 v58, v18, v19 offset1:1
	ds_write2_b32 v58, v20, v21 offset0:2 offset1:3
	ds_write2_b32 v59, v22, v23 offset1:1
	ds_write2_b32 v59, v24, v25 offset0:2 offset1:3
	ds_write2_b32 v60, v26, v27 offset1:1
	ds_write2_b32 v60, v28, v29 offset0:2 offset1:3
	ds_write2_b32 v6, v30, v31 offset1:1
	ds_write2_b32 v7, v32, v33 offset1:1
	ds_write2_b32 v8, v42, v43 offset1:1
	ds_write2_b32 v9, v44, v45 offset1:1
	ds_write2_b32 v10, v46, v47 offset1:1
	ds_write2_b32 v11, v48, v49 offset1:1
	ds_write2_b32 v12, v62, v63 offset1:1
	ds_write2_b32 v13, v64, v65 offset1:1
	s_waitcnt lgkmcnt(0)
	ds_read2_b32 v[14:15], v53 offset1:33
	ds_read2_b32 v[16:17], v53 offset0:66 offset1:99
	ds_read2_b32 v[18:19], v53 offset0:132 offset1:165
	ds_read2_b32 v[20:21], v53 offset0:198 offset1:231
	v_lshl_add_u64 v[22:23], v[66:67], 0, v[74:75]
	s_waitcnt lgkmcnt(0)
	v_cvt_pk_bf16_f32 v14, v14, v15
	s_waitcnt lgkmcnt(2)
	v_cvt_pk_bf16_f32 v15, v16, v17
	s_waitcnt lgkmcnt(1)
	v_cvt_pk_bf16_f32 v16, v18, v19
	s_waitcnt lgkmcnt(0)
	v_cvt_pk_bf16_f32 v17, v20, v21
	global_store_dwordx4 v[68:69], v[14:17], off
	ds_read2_b32 v[14:15], v54 offset1:33
	ds_read2_b32 v[16:17], v54 offset0:66 offset1:99
	ds_read2_b32 v[18:19], v54 offset0:132 offset1:165
	ds_read2_b32 v[20:21], v54 offset0:198 offset1:231
	s_waitcnt lgkmcnt(0)
	v_cvt_pk_bf16_f32 v14, v14, v15
	v_cvt_pk_bf16_f32 v15, v16, v17
	v_cvt_pk_bf16_f32 v16, v18, v19
	v_cvt_pk_bf16_f32 v17, v20, v21
	global_store_dwordx4 v[70:71], v[14:17], off
	ds_read2_b32 v[14:15], v55 offset1:33
	ds_read2_b32 v[16:17], v55 offset0:66 offset1:99
	ds_read2_b32 v[18:19], v55 offset0:132 offset1:165
	ds_read2_b32 v[20:21], v55 offset0:198 offset1:231
	s_waitcnt lgkmcnt(0)
	v_cvt_pk_bf16_f32 v14, v14, v15
	v_cvt_pk_bf16_f32 v15, v16, v17
	v_cvt_pk_bf16_f32 v16, v18, v19
	v_cvt_pk_bf16_f32 v17, v20, v21
	global_store_dwordx4 v[72:73], v[14:17], off
	ds_read2_b32 v[14:15], v56 offset1:33
	ds_read2_b32 v[16:17], v56 offset0:66 offset1:99
	ds_read2_b32 v[18:19], v56 offset0:132 offset1:165
	ds_read2_b32 v[20:21], v56 offset0:198 offset1:231
	s_waitcnt lgkmcnt(0)
	v_cvt_pk_bf16_f32 v14, v14, v15
	v_cvt_pk_bf16_f32 v15, v16, v17
	v_cvt_pk_bf16_f32 v16, v18, v19
	v_cvt_pk_bf16_f32 v17, v20, v21
	global_store_dwordx4 v[22:23], v[14:17], off
	s_waitcnt lgkmcnt(0)
	s_cbranch_scc1 .LBB0_127
	s_branch .LBB0_124

.LBB0_130:
	s_or_b64 exec, exec, s[24:25]
	s_waitcnt vmcnt(0)
	ds_write2_b32 v57, v6, v7 offset1:1
	ds_write2_b32 v57, v8, v9 offset0:2 offset1:3
	ds_write2_b32 v58, v2, v3 offset1:1
	ds_write2_b32 v58, v4, v5 offset0:2 offset1:3
	ds_write2_b32 v59, v14, v15 offset1:1
	ds_write2_b32 v59, v16, v17 offset0:2 offset1:3
	ds_write2_b32 v60, v10, v11 offset1:1
	ds_write2_b32 v60, v12, v13 offset0:2 offset1:3
	v_add_u32_e32 v2, 0x1080, v57
	ds_write2_b32 v2, v22, v23 offset1:1
	v_add_u32_e32 v2, 0x1088, v57
	ds_write2_b32 v2, v24, v25 offset1:1
	v_add_u32_e32 v2, 0x14a0, v57
	ds_write2_b32 v2, v18, v19 offset1:1
	v_add_u32_e32 v2, 0x14a8, v57
	ds_write2_b32 v2, v20, v21 offset1:1
	v_add_u32_e32 v2, 0x18c0, v57
	ds_write2_b32 v2, v30, v31 offset1:1
	v_add_u32_e32 v2, 0x18c8, v57
	ds_write2_b32 v2, v32, v33 offset1:1
	v_add_u32_e32 v2, 0x1ce0, v57
	ds_write2_b32 v2, v26, v27 offset1:1
	v_add_u32_e32 v2, 0x1ce8, v57
	ds_write2_b32 v2, v28, v29 offset1:1
	s_waitcnt lgkmcnt(0)
	ds_read2_b32 v[2:3], v53 offset1:33
	ds_read2_b32 v[4:5], v53 offset0:66 offset1:99
	ds_read2_b32 v[6:7], v53 offset0:132 offset1:165
	ds_read2_b32 v[8:9], v53 offset0:198 offset1:231
	s_ashr_i32 s11, s10, 31
	s_waitcnt lgkmcnt(0)
	v_cvt_pk_bf16_f32 v2, v2, v3
	v_cvt_pk_bf16_f32 v3, v4, v5
	v_cvt_pk_bf16_f32 v4, v6, v7
	v_add_u32_e32 v6, s8, v52
	v_ashrrev_i32_e32 v7, 31, v6
	v_lshl_add_u64 v[10:11], s[10:11], 1, v[44:45]
	v_lshlrev_b64 v[6:7], 11, v[6:7]
	v_cvt_pk_bf16_f32 v5, v8, v9
	v_lshl_add_u64 v[6:7], v[10:11], 0, v[6:7]
	global_store_dwordx4 v[6:7], v[2:5], off
	ds_read2_b32 v[2:3], v54 offset1:33
	ds_read2_b32 v[4:5], v54 offset0:66 offset1:99
	ds_read2_b32 v[6:7], v54 offset0:132 offset1:165
	ds_read2_b32 v[8:9], v54 offset0:198 offset1:231
	s_add_i32 s27, s27, s33
	s_waitcnt lgkmcnt(0)
	v_cvt_pk_bf16_f32 v2, v2, v3
	v_cvt_pk_bf16_f32 v3, v4, v5
	v_cvt_pk_bf16_f32 v4, v6, v7
	v_add_u32_e32 v6, s8, v1
	v_ashrrev_i32_e32 v7, 31, v6
	v_lshlrev_b64 v[6:7], 11, v[6:7]
	v_cvt_pk_bf16_f32 v5, v8, v9
	v_lshl_add_u64 v[6:7], v[10:11], 0, v[6:7]
	global_store_dwordx4 v[6:7], v[2:5], off
	ds_read2_b32 v[2:3], v55 offset1:33
	ds_read2_b32 v[4:5], v55 offset0:66 offset1:99
	ds_read2_b32 v[6:7], v55 offset0:132 offset1:165
	ds_read2_b32 v[8:9], v55 offset0:198 offset1:231
	s_add_i32 s4, s4, s3
	s_waitcnt lgkmcnt(0)
	v_cvt_pk_bf16_f32 v2, v2, v3
	v_cvt_pk_bf16_f32 v3, v4, v5
	v_cvt_pk_bf16_f32 v4, v6, v7
	v_add_u32_e32 v6, s8, v50
	v_ashrrev_i32_e32 v7, 31, v6
	v_lshlrev_b64 v[6:7], 11, v[6:7]
	v_cvt_pk_bf16_f32 v5, v8, v9
	v_lshl_add_u64 v[6:7], v[10:11], 0, v[6:7]
	global_store_dwordx4 v[6:7], v[2:5], off
	ds_read2_b32 v[2:3], v56 offset1:33
	ds_read2_b32 v[4:5], v56 offset0:66 offset1:99
	ds_read2_b32 v[6:7], v56 offset0:132 offset1:165
	ds_read2_b32 v[8:9], v56 offset0:198 offset1:231
	s_cmpk_lt_i32 s27, 0x180
	s_waitcnt lgkmcnt(0)
	v_cvt_pk_bf16_f32 v2, v2, v3
	v_cvt_pk_bf16_f32 v3, v4, v5
	v_cvt_pk_bf16_f32 v4, v6, v7
	v_add_u32_e32 v6, s8, v51
	v_ashrrev_i32_e32 v7, 31, v6
	v_lshlrev_b64 v[6:7], 11, v[6:7]
	v_cvt_pk_bf16_f32 v5, v8, v9
	v_lshl_add_u64 v[6:7], v[10:11], 0, v[6:7]
	global_store_dwordx4 v[6:7], v[2:5], off
	s_waitcnt lgkmcnt(0)
	s_cbranch_scc0 .LBB0_147

.LBB0_149:
	s_or_b64 exec, exec, s[8:9]
	s_waitcnt lgkmcnt(0)
	v_cvt_pk_bf16_f32 v8, v8, v9
	v_cvt_pk_bf16_f32 v9, v10, v11
	v_cvt_pk_bf16_f32 v10, v12, v13
	v_cvt_pk_bf16_f32 v11, v14, v15
	v_mad_i64_i32 v[6:7], s[0:1], v29, s26, v[6:7]
	global_store_dwordx4 v[6:7], v[8:11], off
	s_waitcnt lgkmcnt(0)
	s_add_i32 s27, s27, s33
	s_add_i32 s4, s4, s3
	s_cmpk_lt_i32 s27, 0x120
	s_cbranch_scc0 .LBB0_166
.LBB0_150:
	s_mul_hi_i32 s0, s27, 0x2aaaaaab
	s_lshr_b32 s1, s0, 31
	s_ashr_i32 s0, s0, 3
	s_add_i32 s0, s0, s1
	s_mul_i32 s1, s0, 0xfffffa00
	s_lshl_b32 s8, s0, 6
	s_add_i32 s10, s4, s1
	v_or_b32_e32 v29, s8, v52
	s_ashr_i32 s11, s10, 31
	v_lshl_add_u64 v[6:7], s[10:11], 2, v[2:3]
	v_or_b32_e32 v8, 8, v29
	v_mad_i64_i32 v[30:31], s[10:11], v29, s20, v[6:7]
	v_mad_i64_i32 v[32:33], s[10:11], v8, s20, v[6:7]
	v_or_b32_e32 v35, 32, v29
	global_load_dwordx4 v[8:11], v[30:31], off nt
	global_load_dwordx4 v[12:15], v[32:33], off nt
	v_or_b32_e32 v30, 16, v29
	v_or_b32_e32 v32, 24, v29
	v_mad_i64_i32 v[46:47], s[10:11], v35, s20, v[6:7]
	v_or_b32_e32 v35, 40, v29
	v_mad_i64_i32 v[30:31], s[10:11], v30, s20, v[6:7]
	v_mad_i64_i32 v[42:43], s[10:11], v32, s20, v[6:7]
	v_mad_i64_i32 v[62:63], s[10:11], v35, s20, v[6:7]
	global_load_dwordx4 v[30:33], v[30:31], off nt
	s_nop 0
	global_load_dwordx4 v[42:45], v[42:43], off nt
	s_nop 0
	global_load_dwordx4 v[46:49], v[46:47], off nt
	s_nop 0
	global_load_dwordx4 v[62:65], v[62:63], off nt
	v_or_b32_e32 v35, 48, v29
	v_mad_i64_i32 v[66:67], s[10:11], v35, s20, v[6:7]
	global_load_dwordx4 v[66:69], v[66:67], off nt
	v_or_b32_e32 v29, 56, v29
	v_mad_i64_i32 v[6:7], s[10:11], v29, s20, v[6:7]
	global_load_dwordx4 v[70:73], v[6:7], off nt
	v_add_u32_e32 v7, s4, v52
	v_add_u32_e32 v6, s1, v7
	v_mul_hi_i32 v6, v6, s5
	v_lshrrev_b32_e32 v29, 31, v6
	v_ashrrev_i32_e32 v6, 5, v6
	v_add_u32_e32 v6, v6, v29
	v_mul_lo_u32 v29, v6, s21
	s_mulk_i32 s0, 0x600
	v_subrev_u32_e32 v29, s0, v29
	s_waitcnt vmcnt(0)
	ds_write2_b32 v57, v8, v9 offset1:1
	ds_write2_b32 v57, v10, v11 offset0:2 offset1:3
	ds_write2_b32 v58, v12, v13 offset1:1
	ds_write2_b32 v58, v14, v15 offset0:2 offset1:3
	ds_write2_b32 v59, v30, v31 offset1:1
	ds_write2_b32 v59, v32, v33 offset0:2 offset1:3
	ds_write2_b32 v60, v42, v43 offset1:1
	ds_write2_b32 v60, v44, v45 offset0:2 offset1:3
	ds_write2_b32 v20, v46, v47 offset1:1
	ds_write2_b32 v21, v48, v49 offset1:1
	ds_write2_b32 v22, v62, v63 offset1:1
	ds_write2_b32 v23, v64, v65 offset1:1
	ds_write2_b32 v24, v66, v67 offset1:1
	ds_write2_b32 v25, v68, v69 offset1:1
	ds_write2_b32 v26, v70, v71 offset1:1
	ds_write2_b32 v27, v72, v73 offset1:1
	s_waitcnt lgkmcnt(0)
	ds_read2_b32 v[8:9], v53 offset1:33
	ds_read2_b32 v[10:11], v53 offset0:66 offset1:99
	ds_read2_b32 v[12:13], v53 offset0:132 offset1:165
	ds_read2_b32 v[14:15], v53 offset0:198 offset1:231
	v_add_u32_e32 v30, v7, v29
	v_cmp_lt_i32_e32 vcc, s24, v30
	s_and_saveexec_b64 s[10:11], vcc
	s_xor_b64 s[10:11], exec, s[10:11]
	v_lshlrev_b32_e32 v7, 6, v6
	v_and_b32_e32 v7, 0xffffff00, v7
	v_lshl_add_u32 v29, v30, 2, v28
	v_lshlrev_b32_e32 v6, 5, v6
	v_add_u32_e32 v7, v16, v7
	v_and_b32_e32 v29, 0x7fffff80, v29
	v_and_or_b32 v6, v6, s25, v7
	v_add_u32_e32 v29, v6, v29
	s_andn2_saveexec_b64 s[10:11], s[10:11]
	v_lshl_add_u32 v6, v6, 6, s0
	v_sub_u32_e32 v29, v7, v6
	s_or_b64 exec, exec, s[10:11]
	s_ashr_i32 s9, s8, 31
	v_lshl_add_u64 v[6:7], s[8:9], 1, v[4:5]
	s_waitcnt lgkmcnt(0)
	v_cvt_pk_bf16_f32 v8, v8, v9
	v_cvt_pk_bf16_f32 v9, v10, v11
	v_cvt_pk_bf16_f32 v10, v12, v13
	v_cvt_pk_bf16_f32 v11, v14, v15
	v_mad_i64_i32 v[12:13], s[8:9], v29, s26, v[6:7]
	v_add_u32_e32 v31, s4, v1
	global_store_dwordx4 v[12:13], v[8:11], off
	v_add_u32_e32 v29, s1, v31
	ds_read2_b32 v[8:9], v54 offset1:33
	ds_read2_b32 v[10:11], v54 offset0:66 offset1:99
	ds_read2_b32 v[12:13], v54 offset0:132 offset1:165
	ds_read2_b32 v[14:15], v54 offset0:198 offset1:231
	v_mul_hi_i32 v29, v29, s5
	v_lshrrev_b32_e32 v30, 31, v29
	v_ashrrev_i32_e32 v29, 5, v29
	v_add_u32_e32 v30, v29, v30
	v_mul_lo_u32 v29, v30, s21
	v_subrev_u32_e32 v29, s0, v29
	v_add_u32_e32 v32, v31, v29
	v_cmp_lt_i32_e32 vcc, s24, v32
	s_and_saveexec_b64 s[8:9], vcc
	s_xor_b64 s[8:9], exec, s[8:9]
	v_lshlrev_b32_e32 v29, 6, v30
	v_and_b32_e32 v29, 0xffffff00, v29
	v_lshl_add_u32 v31, v32, 2, v28
	v_lshlrev_b32_e32 v30, 5, v30
	v_add_u32_e32 v29, v17, v29
	v_and_b32_e32 v31, 0x7fffff80, v31
	v_and_or_b32 v29, v30, s25, v29
	v_add_u32_e32 v29, v29, v31
	s_andn2_saveexec_b64 s[8:9], s[8:9]
	v_lshl_add_u32 v29, v30, 6, s0
	v_sub_u32_e32 v29, v31, v29
	s_or_b64 exec, exec, s[8:9]
	s_waitcnt lgkmcnt(0)
	v_cvt_pk_bf16_f32 v8, v8, v9
	v_cvt_pk_bf16_f32 v9, v10, v11
	v_cvt_pk_bf16_f32 v10, v12, v13
	v_cvt_pk_bf16_f32 v11, v14, v15
	v_mad_i64_i32 v[12:13], s[8:9], v29, s26, v[6:7]
	v_add_u32_e32 v31, s4, v50
	global_store_dwordx4 v[12:13], v[8:11], off
	v_add_u32_e32 v29, s1, v31
	ds_read2_b32 v[8:9], v55 offset1:33
	ds_read2_b32 v[10:11], v55 offset0:66 offset1:99
	ds_read2_b32 v[12:13], v55 offset0:132 offset1:165
	ds_read2_b32 v[14:15], v55 offset0:198 offset1:231
	v_mul_hi_i32 v29, v29, s5
	v_lshrrev_b32_e32 v30, 31, v29
	v_ashrrev_i32_e32 v29, 5, v29
	v_add_u32_e32 v30, v29, v30
	v_mul_lo_u32 v29, v30, s21
	v_subrev_u32_e32 v29, s0, v29
	v_add_u32_e32 v32, v31, v29
	v_cmp_lt_i32_e32 vcc, s24, v32
	s_and_saveexec_b64 s[8:9], vcc
	s_xor_b64 s[8:9], exec, s[8:9]
	v_lshlrev_b32_e32 v29, 6, v30
	v_and_b32_e32 v29, 0xffffff00, v29
	v_lshl_add_u32 v31, v32, 2, v28
	v_lshlrev_b32_e32 v30, 5, v30
	v_add_u32_e32 v29, v18, v29
	v_and_b32_e32 v31, 0x7fffff80, v31
	v_and_or_b32 v29, v30, s25, v29
	v_add_u32_e32 v29, v29, v31
	s_andn2_saveexec_b64 s[8:9], s[8:9]
	v_lshl_add_u32 v29, v30, 6, s0
	v_sub_u32_e32 v29, v31, v29
	s_or_b64 exec, exec, s[8:9]
	s_waitcnt lgkmcnt(0)
	v_cvt_pk_bf16_f32 v8, v8, v9
	v_cvt_pk_bf16_f32 v9, v10, v11
	v_cvt_pk_bf16_f32 v10, v12, v13
	v_cvt_pk_bf16_f32 v11, v14, v15
	v_mad_i64_i32 v[12:13], s[8:9], v29, s26, v[6:7]
	v_add_u32_e32 v31, s4, v51
	global_store_dwordx4 v[12:13], v[8:11], off
	v_add_u32_e32 v29, s1, v31
	ds_read2_b32 v[8:9], v56 offset1:33
	ds_read2_b32 v[10:11], v56 offset0:66 offset1:99
	ds_read2_b32 v[12:13], v56 offset0:132 offset1:165
	ds_read2_b32 v[14:15], v56 offset0:198 offset1:231
	v_mul_hi_i32 v29, v29, s5
	v_lshrrev_b32_e32 v30, 31, v29
	v_ashrrev_i32_e32 v29, 5, v29
	v_add_u32_e32 v30, v29, v30
	v_mul_lo_u32 v29, v30, s21
	v_subrev_u32_e32 v29, s0, v29
	v_add_u32_e32 v32, v31, v29
	v_cmp_lt_i32_e32 vcc, s24, v32
	s_and_saveexec_b64 s[8:9], vcc
	s_xor_b64 s[8:9], exec, s[8:9]
	v_lshlrev_b32_e32 v29, 6, v30
	v_and_b32_e32 v29, 0xffffff00, v29
	v_lshl_add_u32 v31, v32, 2, v28
	v_lshlrev_b32_e32 v30, 5, v30
	v_add_u32_e32 v29, v19, v29
	v_and_b32_e32 v31, 0x7fffff80, v31
	v_and_or_b32 v29, v30, s25, v29
	v_add_u32_e32 v29, v29, v31
	s_andn2_saveexec_b64 s[8:9], s[8:9]
	s_cbranch_execz .LBB0_149
	v_lshl_add_u32 v29, v30, 6, s0
	v_sub_u32_e32 v29, v31, v29
	s_branch .LBB0_149

.LBB0_168:
	s_or_b64 exec, exec, s[10:11]
	s_waitcnt vmcnt(0)
	ds_write2_b32 v57, v6, v7 offset1:1
	ds_write2_b32 v57, v8, v9 offset0:2 offset1:3
	ds_write2_b32 v58, v2, v3 offset1:1
	ds_write2_b32 v58, v4, v5 offset0:2 offset1:3
	ds_write2_b32 v59, v14, v15 offset1:1
	ds_write2_b32 v59, v16, v17 offset0:2 offset1:3
	ds_write2_b32 v60, v10, v11 offset1:1
	ds_write2_b32 v60, v12, v13 offset0:2 offset1:3
	v_add_u32_e32 v2, 0x1080, v57
	ds_write2_b32 v2, v22, v23 offset1:1
	v_add_u32_e32 v2, 0x1088, v57
	ds_write2_b32 v2, v24, v25 offset1:1
	v_add_u32_e32 v2, 0x14a0, v57
	ds_write2_b32 v2, v18, v19 offset1:1
	v_add_u32_e32 v2, 0x14a8, v57
	ds_write2_b32 v2, v20, v21 offset1:1
	v_add_u32_e32 v2, 0x18c0, v57
	ds_write2_b32 v2, v30, v31 offset1:1
	v_add_u32_e32 v2, 0x18c8, v57
	ds_write2_b32 v2, v32, v33 offset1:1
	v_add_u32_e32 v2, 0x1ce0, v57
	ds_write2_b32 v2, v26, v27 offset1:1
	v_add_u32_e32 v2, 0x1ce8, v57
	ds_write2_b32 v2, v28, v29 offset1:1
	s_waitcnt lgkmcnt(0)
	ds_read2_b32 v[2:3], v53 offset1:33
	ds_read2_b32 v[4:5], v53 offset0:66 offset1:99
	ds_read2_b32 v[6:7], v53 offset0:132 offset1:165
	ds_read2_b32 v[8:9], v53 offset0:198 offset1:231
	s_sub_i32 s0, 0, s1
	s_add_i32 s0, s0, s4
	s_waitcnt lgkmcnt(0)
	v_cvt_pk_bf16_f32 v2, v2, v3
	v_cvt_pk_bf16_f32 v3, v4, v5
	v_cvt_pk_bf16_f32 v4, v6, v7
	v_add_u32_e32 v6, s0, v52
	s_ashr_i32 s9, s8, 31
	v_ashrrev_i32_e32 v7, 31, v6
	v_lshl_add_u64 v[10:11], s[8:9], 1, v[44:45]
	v_lshlrev_b64 v[6:7], 9, v[6:7]
	v_cvt_pk_bf16_f32 v5, v8, v9
	v_lshl_add_u64 v[6:7], v[10:11], 0, v[6:7]
	global_store_dwordx4 v[6:7], v[2:5], off
	ds_read2_b32 v[2:3], v54 offset1:33
	ds_read2_b32 v[4:5], v54 offset0:66 offset1:99
	ds_read2_b32 v[6:7], v54 offset0:132 offset1:165
	ds_read2_b32 v[8:9], v54 offset0:198 offset1:231
	s_add_i32 s20, s20, s33
	s_waitcnt lgkmcnt(0)
	v_cvt_pk_bf16_f32 v2, v2, v3
	v_cvt_pk_bf16_f32 v3, v4, v5
	v_cvt_pk_bf16_f32 v4, v6, v7
	v_add_u32_e32 v6, s0, v1
	v_ashrrev_i32_e32 v7, 31, v6
	v_lshlrev_b64 v[6:7], 9, v[6:7]
	v_cvt_pk_bf16_f32 v5, v8, v9
	v_lshl_add_u64 v[6:7], v[10:11], 0, v[6:7]
	global_store_dwordx4 v[6:7], v[2:5], off
	ds_read2_b32 v[2:3], v55 offset1:33
	ds_read2_b32 v[4:5], v55 offset0:66 offset1:99
	ds_read2_b32 v[6:7], v55 offset0:132 offset1:165
	ds_read2_b32 v[8:9], v55 offset0:198 offset1:231
	s_add_i32 s4, s4, s3
	s_waitcnt lgkmcnt(0)
	v_cvt_pk_bf16_f32 v2, v2, v3
	v_cvt_pk_bf16_f32 v3, v4, v5
	v_cvt_pk_bf16_f32 v4, v6, v7
	v_add_u32_e32 v6, s0, v50
	v_ashrrev_i32_e32 v7, 31, v6
	v_lshlrev_b64 v[6:7], 9, v[6:7]
	v_cvt_pk_bf16_f32 v5, v8, v9
	v_lshl_add_u64 v[6:7], v[10:11], 0, v[6:7]
	global_store_dwordx4 v[6:7], v[2:5], off
	ds_read2_b32 v[2:3], v56 offset1:33
	ds_read2_b32 v[4:5], v56 offset0:66 offset1:99
	ds_read2_b32 v[6:7], v56 offset0:132 offset1:165
	ds_read2_b32 v[8:9], v56 offset0:198 offset1:231
	s_cmpk_lt_i32 s20, 0x100
	s_waitcnt lgkmcnt(0)
	v_cvt_pk_bf16_f32 v2, v2, v3
	v_cvt_pk_bf16_f32 v3, v4, v5
	v_cvt_pk_bf16_f32 v4, v6, v7
	v_add_u32_e32 v6, s0, v51
	v_ashrrev_i32_e32 v7, 31, v6
	v_lshlrev_b64 v[6:7], 9, v[6:7]
	v_cvt_pk_bf16_f32 v5, v8, v9
	v_lshl_add_u64 v[6:7], v[10:11], 0, v[6:7]
	global_store_dwordx4 v[6:7], v[2:5], off
	s_waitcnt lgkmcnt(0)
	s_cbranch_scc0 .LBB0_185

.LBB0_187:
	s_or_b64 exec, exec, s[8:9]
	s_waitcnt vmcnt(0)
	ds_write2_b32 v57, v6, v7 offset1:1
	ds_write2_b32 v57, v8, v9 offset0:2 offset1:3
	ds_write2_b32 v58, v2, v3 offset1:1
	ds_write2_b32 v58, v4, v5 offset0:2 offset1:3
	ds_write2_b32 v59, v14, v15 offset1:1
	ds_write2_b32 v59, v16, v17 offset0:2 offset1:3
	ds_write2_b32 v60, v10, v11 offset1:1
	ds_write2_b32 v60, v12, v13 offset0:2 offset1:3
	v_add_u32_e32 v2, 0x1080, v57
	ds_write2_b32 v2, v22, v23 offset1:1
	v_add_u32_e32 v2, 0x1088, v57
	ds_write2_b32 v2, v24, v25 offset1:1
	v_add_u32_e32 v2, 0x14a0, v57
	ds_write2_b32 v2, v18, v19 offset1:1
	v_add_u32_e32 v2, 0x14a8, v57
	ds_write2_b32 v2, v20, v21 offset1:1
	v_add_u32_e32 v2, 0x18c0, v57
	ds_write2_b32 v2, v30, v31 offset1:1
	v_add_u32_e32 v2, 0x18c8, v57
	ds_write2_b32 v2, v32, v33 offset1:1
	v_add_u32_e32 v2, 0x1ce0, v57
	ds_write2_b32 v2, v26, v27 offset1:1
	v_add_u32_e32 v2, 0x1ce8, v57
	ds_write2_b32 v2, v28, v29 offset1:1
	s_waitcnt lgkmcnt(0)
	ds_read2_b32 v[2:3], v53 offset1:33
	ds_read2_b32 v[4:5], v53 offset0:66 offset1:99
	ds_read2_b32 v[6:7], v53 offset0:132 offset1:165
	ds_read2_b32 v[8:9], v53 offset0:198 offset1:231
	s_sub_i32 s0, 0, s1
	s_add_i32 s0, s0, s4
	s_waitcnt lgkmcnt(0)
	v_cvt_pk_bf16_f32 v2, v2, v3
	v_cvt_pk_bf16_f32 v3, v4, v5
	v_cvt_pk_bf16_f32 v4, v6, v7
	v_add_u32_e32 v6, s0, v52
	s_ashr_i32 s7, s6, 31
	v_ashrrev_i32_e32 v7, 31, v6
	v_lshl_add_u64 v[10:11], s[6:7], 1, v[40:41]
	v_lshlrev_b64 v[6:7], 11, v[6:7]
	v_cvt_pk_bf16_f32 v5, v8, v9
	v_lshl_add_u64 v[6:7], v[10:11], 0, v[6:7]
	global_store_dwordx4 v[6:7], v[2:5], off
	ds_read2_b32 v[2:3], v54 offset1:33
	ds_read2_b32 v[4:5], v54 offset0:66 offset1:99
	ds_read2_b32 v[6:7], v54 offset0:132 offset1:165
	ds_read2_b32 v[8:9], v54 offset0:198 offset1:231
	s_add_i32 s10, s10, s33
	s_waitcnt lgkmcnt(0)
	v_cvt_pk_bf16_f32 v2, v2, v3
	v_cvt_pk_bf16_f32 v3, v4, v5
	v_cvt_pk_bf16_f32 v4, v6, v7
	v_add_u32_e32 v6, s0, v1
	v_ashrrev_i32_e32 v7, 31, v6
	v_lshlrev_b64 v[6:7], 11, v[6:7]
	v_cvt_pk_bf16_f32 v5, v8, v9
	v_lshl_add_u64 v[6:7], v[10:11], 0, v[6:7]
	global_store_dwordx4 v[6:7], v[2:5], off
	ds_read2_b32 v[2:3], v55 offset1:33
	ds_read2_b32 v[4:5], v55 offset0:66 offset1:99
	ds_read2_b32 v[6:7], v55 offset0:132 offset1:165
	ds_read2_b32 v[8:9], v55 offset0:198 offset1:231
	s_add_i32 s4, s4, s3
	s_waitcnt lgkmcnt(0)
	v_cvt_pk_bf16_f32 v2, v2, v3
	v_cvt_pk_bf16_f32 v3, v4, v5
	v_cvt_pk_bf16_f32 v4, v6, v7
	v_add_u32_e32 v6, s0, v50
	v_ashrrev_i32_e32 v7, 31, v6
	v_lshlrev_b64 v[6:7], 11, v[6:7]
	v_cvt_pk_bf16_f32 v5, v8, v9
	v_lshl_add_u64 v[6:7], v[10:11], 0, v[6:7]
	global_store_dwordx4 v[6:7], v[2:5], off
	ds_read2_b32 v[2:3], v56 offset1:33
	ds_read2_b32 v[4:5], v56 offset0:66 offset1:99
	ds_read2_b32 v[6:7], v56 offset0:132 offset1:165
	ds_read2_b32 v[8:9], v56 offset0:198 offset1:231
	s_cmpk_gt_i32 s10, 0x1ff
	s_waitcnt lgkmcnt(0)
	v_cvt_pk_bf16_f32 v2, v2, v3
	v_cvt_pk_bf16_f32 v3, v4, v5
	v_cvt_pk_bf16_f32 v4, v6, v7
	v_add_u32_e32 v6, s0, v51
	v_ashrrev_i32_e32 v7, 31, v6
	v_lshlrev_b64 v[6:7], 11, v[6:7]
	v_cvt_pk_bf16_f32 v5, v8, v9
	v_lshl_add_u64 v[6:7], v[10:11], 0, v[6:7]
	global_store_dwordx4 v[6:7], v[2:5], off
	s_waitcnt lgkmcnt(0)
	s_cbranch_scc1 .LBB0_204

.LBB0_206:
	global_load_dwordx4 v[10:13], v[4:5], off nt
	v_lshl_add_u64 v[8:9], v[8:9], 0, s[6:7]
	v_cmp_lt_u64_e32 vcc, s[22:23], v[8:9]
	v_lshl_add_u64 v[4:5], v[4:5], 0, s[10:11]
	s_or_b64 s[20:21], vcc, s[20:21]
	s_waitcnt vmcnt(0)
	v_cvt_pk_bf16_f32 v10, v10, v11
	v_cvt_pk_bf16_f32 v11, v12, v13
	global_store_dwordx2 v[6:7], v[10:11], off
	v_lshl_add_u64 v[6:7], v[6:7], 0, s[16:17]
	s_andn2_b64 exec, exec, s[20:21]
	s_cbranch_execnz .LBB0_206

.LBB0_209:
	v_lshrrev_b64 v[8:9], 3, v[2:3]
	v_and_b32_e32 v8, -4, v8
	v_lshl_add_u64 v[8:9], s[18:19], 0, v[8:9]
	global_load_dword v7, v[8:9], off
	v_add_co_u32_e32 v8, vcc, 0xff800000, v4
	v_lshl_add_u64 v[2:3], v[2:3], 0, s[6:7]
	s_nop 0
	v_addc_co_u32_e32 v9, vcc, -1, v5, vcc
	v_cmp_lt_u64_e32 vcc, s[24:25], v[2:3]
	s_or_b64 s[16:17], vcc, s[16:17]
	s_waitcnt vmcnt(0)
	v_cvt_f32_i32_e32 v7, v7
	v_mul_f32_e32 v7, v6, v7
	v_cvt_f64_f32_e32 v[10:11], v7
	v_mul_f64 v[12:13], v[10:11], s[20:21]
	v_rndne_f64_e32 v[12:13], v[12:13]
	v_fmac_f64_e32 v[10:11], s[22:23], v[12:13]
	v_cvt_f32_f64_e32 v7, v[10:11]
	v_mul_f32_e32 v7, 0.15915494, v7
	v_cos_f32_e32 v10, v7
	v_sin_f32_e32 v7, v7
	global_store_dword v[8:9], v10, off
	global_store_dword v[4:5], v7, off
	v_lshl_add_u64 v[4:5], v[4:5], 0, s[10:11]
	s_andn2_b64 exec, exec, s[16:17]
	s_cbranch_execnz .LBB0_209

.LBB0_213:
	s_mul_hi_i32 s0, s18, 0x2aaaaaab
	s_lshr_b32 s1, s0, 31
	s_ashr_i32 s0, s0, 8
	s_add_i32 s8, s0, s1
	s_mul_i32 s0, s8, 0xfffffa00
	s_add_i32 s21, s18, s0
	s_lshr_b32 s0, s21, 22
	s_and_b32 s0, s0, 0x1ff
	s_add_i32 s22, s21, s0
	s_and_b32 s0, s22, 0xfe00
	s_sub_i32 s0, s21, s0
	s_sext_i32_i16 s1, s0
	s_bfe_u32 s1, s1, 0x5001a
	s_add_i32 s1, s0, s1
	s_sext_i32_i16 s6, s1
	s_and_b32 s1, s1, 0xffe0
	s_lshl_b32 s20, s6, 1
	s_sub_i32 s0, s0, s1
	s_andn2_b32 s20, s20, 63
	s_sext_i32_i16 s19, s0
	s_lshl_b32 s6, s19, 5
	v_or_b32_e32 v16, s20, v52
	s_mov_b64 s[10:11], -1
	s_cmpk_gt_i32 s21, 0x3ff
	v_ashrrev_i32_e32 v17, 31, v16
	v_or_b32_e32 v14, 8, v16
	v_or_b32_e32 v12, 16, v16
	v_or_b32_e32 v10, 24, v16
	v_or_b32_e32 v8, 32, v16
	v_or_b32_e32 v6, 40, v16
	v_or_b32_e32 v4, 48, v16
	v_or_b32_e32 v2, 56, v16
	s_cbranch_scc0 .LBB0_215
	s_ashr_i32 s9, s8, 31
	s_lshl_b64 s[0:1], s[8:9], 20
	s_lshl_b64 s[10:11], s[8:9], 22
	s_add_u32 s9, s34, s10
	s_addc_u32 s10, s35, s11
	s_add_u32 s11, s5, s0
	s_addc_u32 s23, s16, s1
	s_ashr_i32 s7, s6, 31
	s_lshl_b64 s[0:1], s[6:7], 2
	s_add_u32 s0, s9, s0
	s_addc_u32 s1, s10, s1
	v_lshl_add_u64 v[48:49], v[36:37], 2, s[0:1]
	v_lshlrev_b64 v[28:29], 12, v[16:17]
	v_ashrrev_i32_e32 v15, 31, v14
	v_lshl_add_u64 v[40:41], v[48:49], 0, v[28:29]
	v_lshlrev_b64 v[28:29], 12, v[14:15]
	v_ashrrev_i32_e32 v13, 31, v12
	v_lshl_add_u64 v[42:43], v[48:49], 0, v[28:29]
	global_load_dwordx4 v[28:31], v[40:41], off nt
	global_load_dwordx4 v[32:35], v[42:43], off nt
	v_lshlrev_b64 v[40:41], 12, v[12:13]
	v_ashrrev_i32_e32 v11, 31, v10
	v_lshl_add_u64 v[62:63], v[48:49], 0, v[40:41]
	v_lshlrev_b64 v[40:41], 12, v[10:11]
	v_ashrrev_i32_e32 v9, 31, v8
	v_lshl_add_u64 v[64:65], v[48:49], 0, v[40:41]
	global_load_dwordx4 v[40:43], v[62:63], off nt
	global_load_dwordx4 v[44:47], v[64:65], off nt
	v_lshlrev_b64 v[62:63], 12, v[8:9]
	v_ashrrev_i32_e32 v7, 31, v6
	v_lshl_add_u64 v[70:71], v[48:49], 0, v[62:63]
	v_lshlrev_b64 v[62:63], 12, v[6:7]
	v_lshl_add_u64 v[72:73], v[48:49], 0, v[62:63]
	global_load_dwordx4 v[62:65], v[70:71], off nt
	global_load_dwordx4 v[66:69], v[72:73], off nt
	v_ashrrev_i32_e32 v5, 31, v4
	v_lshlrev_b64 v[70:71], 12, v[4:5]
	v_lshl_add_u64 v[70:71], v[48:49], 0, v[70:71]
	v_ashrrev_i32_e32 v3, 31, v2
	global_load_dwordx4 v[70:73], v[70:71], off nt
	v_lshlrev_b64 v[74:75], 12, v[2:3]
	v_lshl_add_u64 v[48:49], v[48:49], 0, v[74:75]
	global_load_dwordx4 v[74:77], v[48:49], off nt
	v_mov_b32_e32 v48, 0
	v_mov_b32_e32 v49, 0
	s_ashr_i32 s1, s20, 31
	v_or_b32_e32 v78, s6, v52
	s_add_u32 s0, s11, s20
	v_ashrrev_i32_e32 v79, 31, v78
	s_addc_u32 s1, s23, s1
	v_lshlrev_b64 v[78:79], 10, v[78:79]
	v_mov_b32_e32 v80, 0
	v_mov_b32_e32 v81, 0
	s_waitcnt vmcnt(0)
	ds_write2_b32 v57, v28, v29 offset1:1
	ds_write2_b32 v57, v30, v31 offset0:2 offset1:3
	ds_write2_b32 v58, v32, v33 offset1:1
	ds_write2_b32 v58, v34, v35 offset0:2 offset1:3
	ds_write2_b32 v59, v40, v41 offset1:1
	ds_write2_b32 v59, v42, v43 offset0:2 offset1:3
	ds_write2_b32 v60, v44, v45 offset1:1
	ds_write2_b32 v60, v46, v47 offset0:2 offset1:3
	ds_write2_b32 v18, v62, v63 offset1:1
	ds_write2_b32 v19, v64, v65 offset1:1
	ds_write2_b32 v20, v66, v67 offset1:1
	ds_write2_b32 v21, v68, v69 offset1:1
	ds_write2_b32 v22, v70, v71 offset1:1
	ds_write2_b32 v23, v72, v73 offset1:1
	ds_write2_b32 v24, v74, v75 offset1:1
	ds_write2_b32 v25, v76, v77 offset1:1
	s_waitcnt lgkmcnt(0)
	ds_read2_b32 v[28:29], v53 offset1:33
	ds_read2_b32 v[30:31], v53 offset0:66 offset1:99
	ds_read2_b32 v[32:33], v53 offset0:132 offset1:165
	ds_read2_b32 v[34:35], v53 offset0:198 offset1:231
	s_waitcnt lgkmcnt(0)
	v_mul_f32_e32 v7, 0x43000000, v30
	v_mul_f32_e32 v3, 0x43000000, v28
	v_mul_f32_e32 v5, 0x43000000, v29
	v_mul_f32_e32 v11, 0x43000000, v32
	v_mul_f32_e32 v13, 0x43000000, v33
	v_med3_f32 v3, v3, s17, v26
	v_med3_f32 v5, v5, s17, v26
	v_med3_f32 v11, v11, s17, v26
	v_med3_f32 v13, v13, s17, v26
	v_cvt_pk_fp8_f32 v48, v3, v5
	v_cvt_pk_fp8_f32 v49, v11, v13
	v_mul_f32_e32 v9, 0x43000000, v31
	v_mul_f32_e32 v15, 0x43000000, v34
	v_mul_f32_e32 v27, 0x43000000, v35
	v_med3_f32 v7, v7, s17, v26
	v_med3_f32 v9, v9, s17, v26
	v_med3_f32 v3, v15, s17, v26
	v_med3_f32 v5, v27, s17, v26
	v_cvt_pk_fp8_f32 v48, v7, v9 op_sel:[0,0,1]
	v_cvt_pk_fp8_f32 v49, v3, v5 op_sel:[0,0,1]
	v_lshl_add_u64 v[28:29], s[0:1], 0, v[38:39]
	v_lshl_add_u64 v[30:31], v[28:29], 0, v[78:79]
	global_store_dwordx2 v[30:31], v[48:49], off
	ds_read2_b32 v[30:31], v54 offset1:33
	ds_read2_b32 v[32:33], v54 offset0:66 offset1:99
	ds_read2_b32 v[34:35], v54 offset0:132 offset1:165
	ds_read2_b32 v[40:41], v54 offset0:198 offset1:231
	s_waitcnt lgkmcnt(0)
	v_mul_f32_e32 v7, 0x43000000, v32
	v_mul_f32_e32 v3, 0x43000000, v30
	v_mul_f32_e32 v5, 0x43000000, v31
	v_mul_f32_e32 v11, 0x43000000, v34
	v_mul_f32_e32 v13, 0x43000000, v35
	v_med3_f32 v3, v3, s17, v26
	v_med3_f32 v5, v5, s17, v26
	v_med3_f32 v11, v11, s17, v26
	v_med3_f32 v13, v13, s17, v26
	v_cvt_pk_fp8_f32 v80, v3, v5
	v_cvt_pk_fp8_f32 v81, v11, v13
	v_mul_f32_e32 v9, 0x43000000, v33
	v_mul_f32_e32 v15, 0x43000000, v40
	v_mul_f32_e32 v27, 0x43000000, v41
	v_med3_f32 v7, v7, s17, v26
	v_med3_f32 v9, v9, s17, v26
	v_med3_f32 v3, v15, s17, v26
	v_med3_f32 v5, v27, s17, v26
	v_cvt_pk_fp8_f32 v80, v7, v9 op_sel:[0,0,1]
	v_cvt_pk_fp8_f32 v81, v3, v5 op_sel:[0,0,1]
	v_or_b32_e32 v30, s6, v1
	v_ashrrev_i32_e32 v31, 31, v30
	v_lshlrev_b64 v[30:31], 10, v[30:31]
	v_lshl_add_u64 v[30:31], v[28:29], 0, v[30:31]
	global_store_dwordx2 v[30:31], v[80:81], off
	ds_read2_b32 v[30:31], v55 offset1:33
	ds_read2_b32 v[32:33], v55 offset0:66 offset1:99
	ds_read2_b32 v[34:35], v55 offset0:198 offset1:231
	s_waitcnt lgkmcnt(0)
	v_mul_f32_e32 v3, 0x43000000, v30
	v_mul_f32_e32 v5, 0x43000000, v31
	v_mul_f32_e32 v7, 0x43000000, v32
	v_mul_f32_e32 v9, 0x43000000, v33
	v_med3_f32 v3, v3, s17, v26
	v_med3_f32 v5, v5, s17, v26
	v_mov_b32_e32 v30, 0
	ds_read2_b32 v[32:33], v55 offset0:132 offset1:165
	v_cvt_pk_fp8_f32 v30, v3, v5
	v_med3_f32 v3, v7, s17, v26
	v_med3_f32 v5, v9, s17, v26
	v_mov_b32_e32 v31, 0
	v_cvt_pk_fp8_f32 v30, v3, v5 op_sel:[0,0,1]
	s_waitcnt lgkmcnt(0)
	v_mul_f32_e32 v3, 0x43000000, v32
	v_mul_f32_e32 v5, 0x43000000, v33
	v_med3_f32 v3, v3, s17, v26
	v_med3_f32 v5, v5, s17, v26
	v_cvt_pk_fp8_f32 v31, v3, v5
	v_mul_f32_e32 v7, 0x43000000, v34
	v_mul_f32_e32 v3, 0x43000000, v35
	v_med3_f32 v5, v7, s17, v26
	v_med3_f32 v3, v3, s17, v26
	v_cvt_pk_fp8_f32 v31, v5, v3 op_sel:[0,0,1]
	v_or_b32_e32 v32, s6, v50
	v_ashrrev_i32_e32 v33, 31, v32
	v_lshlrev_b64 v[32:33], 10, v[32:33]
	v_lshl_add_u64 v[32:33], v[28:29], 0, v[32:33]
	global_store_dwordx2 v[32:33], v[30:31], off
	ds_read2_b32 v[30:31], v56 offset1:33
	ds_read2_b32 v[32:33], v56 offset0:66 offset1:99
	ds_read2_b32 v[34:35], v56 offset0:198 offset1:231
	s_waitcnt lgkmcnt(0)
	v_mul_f32_e32 v3, 0x43000000, v30
	v_mul_f32_e32 v5, 0x43000000, v31
	v_mul_f32_e32 v7, 0x43000000, v32
	v_mul_f32_e32 v9, 0x43000000, v33
	v_med3_f32 v3, v3, s17, v26
	v_med3_f32 v5, v5, s17, v26
	v_mov_b32_e32 v30, 0
	ds_read2_b32 v[32:33], v56 offset0:132 offset1:165
	v_cvt_pk_fp8_f32 v30, v3, v5
	v_med3_f32 v3, v7, s17, v26
	v_med3_f32 v5, v9, s17, v26
	v_mov_b32_e32 v31, 0
	v_cvt_pk_fp8_f32 v30, v3, v5 op_sel:[0,0,1]
	s_waitcnt lgkmcnt(0)
	v_mul_f32_e32 v3, 0x43000000, v32
	v_mul_f32_e32 v5, 0x43000000, v33
	v_med3_f32 v3, v3, s17, v26
	v_med3_f32 v5, v5, s17, v26
	v_cvt_pk_fp8_f32 v31, v3, v5
	v_mul_f32_e32 v7, 0x43000000, v34
	v_mul_f32_e32 v3, 0x43000000, v35
	v_med3_f32 v5, v7, s17, v26
	v_med3_f32 v3, v3, s17, v26
	v_cvt_pk_fp8_f32 v31, v5, v3 op_sel:[0,0,1]
	v_or_b32_e32 v32, s6, v51
	v_ashrrev_i32_e32 v33, 31, v32
	v_lshlrev_b64 v[32:33], 10, v[32:33]
	v_lshl_add_u64 v[28:29], v[28:29], 0, v[32:33]
	global_store_dwordx2 v[28:29], v[30:31], off
	s_waitcnt lgkmcnt(0)
	s_cbranch_execnz .LBB0_212
	s_branch .LBB0_216

.LBB0_216:
	s_sext_i32_i16 s0, s22
	s_lshr_b32 s10, s0, 9
	s_addk_i32 s21, 0x1ff
	s_cmpk_lt_u32 s21, 0x3ff
	s_cselect_b32 s7, s13, s15
	s_cselect_b32 s11, s12, s14
	s_ashr_i32 s9, s8, 31
	s_lshl_b64 s[0:1], s[8:9], 22
	s_add_u32 s11, s11, s0
	s_addc_u32 s21, s7, s1
	s_lshl_b64 s[0:1], s[8:9], 21
	s_add_u32 s8, s3, s0
	s_addc_u32 s9, s4, s1
	s_ashr_i32 s7, s6, 31
	s_lshl_b64 s[0:1], s[6:7], 2
	s_add_u32 s0, s11, s0
	s_addc_u32 s1, s21, s1
	v_ashrrev_i32_e32 v15, 31, v14
	v_ashrrev_i32_e32 v13, 31, v12
	v_ashrrev_i32_e32 v11, 31, v10
	v_ashrrev_i32_e32 v9, 31, v8
	v_lshl_add_u64 v[48:49], v[36:37], 2, s[0:1]
	v_lshlrev_b64 v[16:17], 12, v[16:17]
	v_lshlrev_b64 v[14:15], 12, v[14:15]
	v_lshlrev_b64 v[12:13], 12, v[12:13]
	v_lshlrev_b64 v[10:11], 12, v[10:11]
	v_lshlrev_b64 v[8:9], 12, v[8:9]
	v_ashrrev_i32_e32 v7, 31, v6
	v_lshl_add_u64 v[32:33], v[48:49], 0, v[16:17]
	v_lshl_add_u64 v[34:35], v[48:49], 0, v[14:15]
	v_lshl_add_u64 v[40:41], v[48:49], 0, v[12:13]
	v_lshl_add_u64 v[42:43], v[48:49], 0, v[10:11]
	v_lshl_add_u64 v[44:45], v[48:49], 0, v[8:9]
	v_lshlrev_b64 v[6:7], 12, v[6:7]
	global_load_dwordx4 v[14:17], v[32:33], off nt
	global_load_dwordx4 v[28:31], v[34:35], off nt
	global_load_dwordx4 v[10:13], v[40:41], off nt
	s_nop 0
	global_load_dwordx4 v[32:35], v[42:43], off nt
	v_lshl_add_u64 v[46:47], v[48:49], 0, v[6:7]
	global_load_dwordx4 v[6:9], v[44:45], off nt
	global_load_dwordx4 v[40:43], v[46:47], off nt
	v_ashrrev_i32_e32 v5, 31, v4
	v_lshlrev_b64 v[4:5], 12, v[4:5]
	v_lshl_add_u64 v[4:5], v[48:49], 0, v[4:5]
	v_ashrrev_i32_e32 v3, 31, v2
	global_load_dwordx4 v[44:47], v[4:5], off nt
	v_lshlrev_b64 v[2:3], 12, v[2:3]
	v_lshl_add_u64 v[2:3], v[48:49], 0, v[2:3]
	global_load_dwordx4 v[2:5], v[2:3], off nt
	s_sext_i32_i16 s0, s10
	s_lshl_b32 s7, s0, 7
	s_ashr_i32 s1, s20, 31
	v_mov_b32_e32 v48, 0
	v_mov_b32_e32 v49, 0
	s_add_u32 s0, s8, s20
	s_addc_u32 s1, s9, s1
	s_lshl_b32 s8, s19, 6
	v_lshl_add_u64 v[62:63], s[0:1], 0, v[38:39]
	s_and_b32 s0, s8, 0xffffff00
	s_and_b32 s6, s6, 0x60
	s_add_i32 s0, s0, s7
	s_or_b32 s0, s0, s6
	s_waitcnt vmcnt(0)
	ds_write2_b32 v57, v14, v15 offset1:1
	ds_write2_b32 v57, v16, v17 offset0:2 offset1:3
	ds_write2_b32 v58, v28, v29 offset1:1
	ds_write2_b32 v58, v30, v31 offset0:2 offset1:3
	ds_write2_b32 v59, v10, v11 offset1:1
	ds_write2_b32 v59, v12, v13 offset0:2 offset1:3
	ds_write2_b32 v60, v32, v33 offset1:1
	ds_write2_b32 v60, v34, v35 offset0:2 offset1:3
	ds_write2_b32 v18, v6, v7 offset1:1
	ds_write2_b32 v19, v8, v9 offset1:1
	ds_write2_b32 v20, v40, v41 offset1:1
	ds_write2_b32 v21, v42, v43 offset1:1
	ds_write2_b32 v22, v44, v45 offset1:1
	ds_write2_b32 v23, v46, v47 offset1:1
	ds_write2_b32 v24, v2, v3 offset1:1
	ds_write2_b32 v25, v4, v5 offset1:1
	s_waitcnt lgkmcnt(0)
	ds_read2_b32 v[2:3], v53 offset1:33
	ds_read2_b32 v[6:7], v53 offset0:66 offset1:99
	ds_read2_b32 v[8:9], v53 offset0:132 offset1:165
	ds_read2_b32 v[10:11], v53 offset0:198 offset1:231
	v_or_b32_e32 v4, s0, v52
	s_waitcnt lgkmcnt(0)
	v_mul_f32_e32 v5, 0x42800000, v6
	v_mul_f32_e32 v2, 0x42800000, v2
	v_mul_f32_e32 v3, 0x42800000, v3
	v_mul_f32_e32 v6, 0x42800000, v7
	v_mul_f32_e32 v7, 0x42800000, v8
	v_mul_f32_e32 v8, 0x42800000, v9
	v_med3_f32 v2, v2, s17, v26
	v_med3_f32 v3, v3, s17, v26
	v_med3_f32 v7, v7, s17, v26
	v_med3_f32 v8, v8, s17, v26
	v_cvt_pk_fp8_f32 v48, v2, v3
	v_cvt_pk_fp8_f32 v49, v7, v8
	v_mul_f32_e32 v9, 0x42800000, v10
	v_mul_f32_e32 v10, 0x42800000, v11
	v_med3_f32 v5, v5, s17, v26
	v_med3_f32 v6, v6, s17, v26
	v_med3_f32 v2, v9, s17, v26
	v_med3_f32 v3, v10, s17, v26
	v_cvt_pk_fp8_f32 v48, v5, v6 op_sel:[0,0,1]
	v_cvt_pk_fp8_f32 v49, v2, v3 op_sel:[0,0,1]
	v_ashrrev_i32_e32 v5, 31, v4
	v_lshlrev_b64 v[2:3], 10, v[4:5]
	v_lshl_add_u64 v[2:3], v[62:63], 0, v[2:3]
	global_store_dwordx2 v[2:3], v[48:49], off
	ds_read2_b32 v[2:3], v54 offset1:33
	v_mov_b32_e32 v4, 0
	ds_read2_b32 v[6:7], v54 offset0:66 offset1:99
	ds_read2_b32 v[8:9], v54 offset0:132 offset1:165
	ds_read2_b32 v[10:11], v54 offset0:198 offset1:231
	s_waitcnt lgkmcnt(0)
	v_mul_f32_e32 v2, 0x42800000, v2
	v_mul_f32_e32 v3, 0x42800000, v3
	v_med3_f32 v2, v2, s17, v26
	v_med3_f32 v3, v3, s17, v26
	v_cvt_pk_fp8_f32 v4, v2, v3
	v_mul_f32_e32 v5, 0x42800000, v6
	v_mul_f32_e32 v6, 0x42800000, v7
	v_med3_f32 v3, v5, s17, v26
	v_med3_f32 v5, v6, s17, v26
	v_mul_f32_e32 v2, 0x42800000, v8
	v_cvt_pk_fp8_f32 v4, v3, v5 op_sel:[0,0,1]
	v_mul_f32_e32 v3, 0x42800000, v9
	v_med3_f32 v2, v2, s17, v26
	v_med3_f32 v3, v3, s17, v26
	v_mov_b32_e32 v5, 0
	v_cvt_pk_fp8_f32 v5, v2, v3
	v_mul_f32_e32 v6, 0x42800000, v10
	v_mul_f32_e32 v2, 0x42800000, v11
	v_med3_f32 v3, v6, s17, v26
	v_med3_f32 v2, v2, s17, v26
	v_cvt_pk_fp8_f32 v5, v3, v2 op_sel:[0,0,1]
	v_or_b32_e32 v2, s0, v1
	v_ashrrev_i32_e32 v3, 31, v2
	v_lshlrev_b64 v[2:3], 10, v[2:3]
	v_lshl_add_u64 v[2:3], v[62:63], 0, v[2:3]
	global_store_dwordx2 v[2:3], v[4:5], off
	ds_read2_b32 v[2:3], v55 offset1:33
	ds_read2_b32 v[4:5], v55 offset0:66 offset1:99
	s_waitcnt lgkmcnt(0)
	v_mul_f32_e32 v2, 0x42800000, v2
	v_mul_f32_e32 v3, 0x42800000, v3
	v_mul_f32_e32 v6, 0x42800000, v4
	v_med3_f32 v4, v2, s17, v26
	v_med3_f32 v3, v3, s17, v26
	v_mov_b32_e32 v2, 0
	v_mul_f32_e32 v8, 0x42800000, v5
	v_cvt_pk_fp8_f32 v2, v4, v3
	ds_read2_b32 v[4:5], v55 offset0:132 offset1:165
	v_med3_f32 v3, v6, s17, v26
	ds_read2_b32 v[6:7], v55 offset0:198 offset1:231
	v_med3_f32 v8, v8, s17, v26
	v_cvt_pk_fp8_f32 v2, v3, v8 op_sel:[0,0,1]
	s_waitcnt lgkmcnt(0)
	v_mul_f32_e32 v3, 0x42800000, v4
	v_mul_f32_e32 v4, 0x42800000, v5
	v_mul_f32_e32 v5, 0x42800000, v6
	v_med3_f32 v6, v3, s17, v26
	v_med3_f32 v4, v4, s17, v26
	v_mov_b32_e32 v3, 0
	v_cvt_pk_fp8_f32 v3, v6, v4
	v_mul_f32_e32 v4, 0x42800000, v7
	v_med3_f32 v5, v5, s17, v26
	v_med3_f32 v4, v4, s17, v26
	v_cvt_pk_fp8_f32 v3, v5, v4 op_sel:[0,0,1]
	v_or_b32_e32 v4, s0, v50
	v_ashrrev_i32_e32 v5, 31, v4
	v_lshlrev_b64 v[4:5], 10, v[4:5]
	v_lshl_add_u64 v[4:5], v[62:63], 0, v[4:5]
	global_store_dwordx2 v[4:5], v[2:3], off
	ds_read2_b32 v[2:3], v56 offset1:33
	ds_read2_b32 v[4:5], v56 offset0:66 offset1:99
	s_waitcnt lgkmcnt(0)
	v_mul_f32_e32 v2, 0x42800000, v2
	v_mul_f32_e32 v3, 0x42800000, v3
	v_mul_f32_e32 v6, 0x42800000, v4
	v_med3_f32 v4, v2, s17, v26
	v_med3_f32 v3, v3, s17, v26
	v_mov_b32_e32 v2, 0
	v_mul_f32_e32 v8, 0x42800000, v5
	v_cvt_pk_fp8_f32 v2, v4, v3
	ds_read2_b32 v[4:5], v56 offset0:132 offset1:165
	v_med3_f32 v3, v6, s17, v26
	ds_read2_b32 v[6:7], v56 offset0:198 offset1:231
	v_med3_f32 v8, v8, s17, v26
	v_cvt_pk_fp8_f32 v2, v3, v8 op_sel:[0,0,1]
	s_waitcnt lgkmcnt(0)
	v_mul_f32_e32 v3, 0x42800000, v4
	v_mul_f32_e32 v4, 0x42800000, v5
	v_mul_f32_e32 v5, 0x42800000, v6
	v_med3_f32 v6, v3, s17, v26
	v_med3_f32 v4, v4, s17, v26
	v_mov_b32_e32 v3, 0
	v_cvt_pk_fp8_f32 v3, v6, v4
	v_mul_f32_e32 v4, 0x42800000, v7
	v_med3_f32 v5, v5, s17, v26
	v_med3_f32 v4, v4, s17, v26
	v_cvt_pk_fp8_f32 v3, v5, v4 op_sel:[0,0,1]
	v_or_b32_e32 v4, s0, v51
	v_ashrrev_i32_e32 v5, 31, v4
	v_lshlrev_b64 v[4:5], 10, v[4:5]
	v_lshl_add_u64 v[4:5], v[62:63], 0, v[4:5]
	global_store_dwordx2 v[4:5], v[2:3], off
	s_waitcnt lgkmcnt(0)
	s_branch .LBB0_212

.LBB0_284:
	s_lshl_b32 s0, s28, 8
	s_add_i32 s0, s0, s47
	v_add_u32_e32 v170, s0, v162
	v_mov_b32_e32 v164, v170
	v_lshlrev_b64 v[154:155], 2, v[154:155]
	v_ashrrev_i32_e32 v165, 31, v164
	v_lshlrev_b64 v[164:165], 6, v[164:165]
	v_lshl_add_u64 v[164:165], s[10:11], 0, v[164:165]
	v_lshl_add_u64 v[168:169], v[164:165], 0, v[154:155]
	s_waitcnt vmcnt(0)
	v_pk_add_f32 v[166:167], v[128:129], v[132:133]
	v_pk_add_f32 v[164:165], v[126:127], v[130:131]
	global_store_dwordx4 v[168:169], v[164:167], off
	s_nop 1
	v_pk_add_f32 v[166:167], v[124:125], v[136:137]
	v_pk_add_f32 v[164:165], v[122:123], v[134:135]
	global_store_dwordx4 v[168:169], v[164:167], off offset:16
	s_nop 1
	v_add_u32_e32 v164, 16, v170
	v_pk_add_f32 v[166:167], v[120:121], v[132:133]
	v_ashrrev_i32_e32 v165, 31, v164
	v_lshlrev_b64 v[164:165], 6, v[164:165]
	v_lshl_add_u64 v[164:165], s[10:11], 0, v[164:165]
	v_lshl_add_u64 v[168:169], v[164:165], 0, v[154:155]
	v_pk_add_f32 v[164:165], v[118:119], v[130:131]
	global_store_dwordx4 v[168:169], v[164:167], off
	s_nop 1
	v_pk_add_f32 v[166:167], v[112:113], v[136:137]
	v_pk_add_f32 v[164:165], v[110:111], v[134:135]
	global_store_dwordx4 v[168:169], v[164:167], off offset:16
	s_nop 1
	v_add_u32_e32 v164, 32, v170
	v_pk_add_f32 v[166:167], v[104:105], v[132:133]
	v_ashrrev_i32_e32 v165, 31, v164
	v_lshlrev_b64 v[164:165], 6, v[164:165]
	v_lshl_add_u64 v[164:165], s[10:11], 0, v[164:165]
	v_lshl_add_u64 v[168:169], v[164:165], 0, v[154:155]
	v_pk_add_f32 v[164:165], v[102:103], v[130:131]
	global_store_dwordx4 v[168:169], v[164:167], off
	s_nop 1
	v_pk_add_f32 v[166:167], v[96:97], v[136:137]
	v_pk_add_f32 v[164:165], v[94:95], v[134:135]
	global_store_dwordx4 v[168:169], v[164:167], off offset:16
	s_nop 1
	v_add_u32_e32 v164, 48, v170
	v_pk_add_f32 v[166:167], v[88:89], v[132:133]
	v_ashrrev_i32_e32 v165, 31, v164
	v_lshlrev_b64 v[164:165], 6, v[164:165]
	v_lshl_add_u64 v[164:165], s[10:11], 0, v[164:165]
	v_lshl_add_u64 v[168:169], v[164:165], 0, v[154:155]
	v_pk_add_f32 v[164:165], v[86:87], v[130:131]
	global_store_dwordx4 v[168:169], v[164:167], off
	s_nop 1
	v_pk_add_f32 v[166:167], v[80:81], v[136:137]
	v_pk_add_f32 v[164:165], v[78:79], v[134:135]
	global_store_dwordx4 v[168:169], v[164:167], off offset:16
	s_nop 1
	v_add_u32_e32 v164, 0x80, v170
	v_pk_add_f32 v[166:167], v[64:65], v[132:133]
	v_ashrrev_i32_e32 v165, 31, v164
	v_lshlrev_b64 v[164:165], 6, v[164:165]
	v_lshl_add_u64 v[164:165], s[10:11], 0, v[164:165]
	v_lshl_add_u64 v[168:169], v[164:165], 0, v[154:155]
	v_pk_add_f32 v[164:165], v[62:63], v[130:131]
	global_store_dwordx4 v[168:169], v[164:167], off
	s_nop 1
	v_pk_add_f32 v[166:167], v[60:61], v[136:137]
	v_pk_add_f32 v[164:165], v[58:59], v[134:135]
	global_store_dwordx4 v[168:169], v[164:167], off offset:16
	s_nop 1
	v_add_u32_e32 v164, 0x90, v170
	v_pk_add_f32 v[166:167], v[56:57], v[132:133]
	v_ashrrev_i32_e32 v165, 31, v164
	v_lshlrev_b64 v[164:165], 6, v[164:165]
	v_lshl_add_u64 v[164:165], s[10:11], 0, v[164:165]
	v_lshl_add_u64 v[168:169], v[164:165], 0, v[154:155]
	v_pk_add_f32 v[164:165], v[54:55], v[130:131]
	global_store_dwordx4 v[168:169], v[164:167], off
	s_nop 1
	v_pk_add_f32 v[166:167], v[48:49], v[136:137]
	v_pk_add_f32 v[164:165], v[46:47], v[134:135]
	global_store_dwordx4 v[168:169], v[164:167], off offset:16
	s_nop 1
	v_add_u32_e32 v164, 0xa0, v170
	v_pk_add_f32 v[166:167], v[40:41], v[132:133]
	v_ashrrev_i32_e32 v165, 31, v164
	v_lshlrev_b64 v[164:165], 6, v[164:165]
	v_lshl_add_u64 v[164:165], s[10:11], 0, v[164:165]
	v_lshl_add_u64 v[168:169], v[164:165], 0, v[154:155]
	v_pk_add_f32 v[164:165], v[38:39], v[130:131]
	global_store_dwordx4 v[168:169], v[164:167], off
	v_pk_add_f32 v[132:133], v[24:25], v[132:133]
	v_pk_add_f32 v[130:131], v[22:23], v[130:131]
	v_pk_add_f32 v[166:167], v[32:33], v[136:137]
	v_pk_add_f32 v[164:165], v[30:31], v[134:135]
	global_store_dwordx4 v[168:169], v[164:167], off offset:16
	s_nop 1
	v_add_u32_e32 v164, 0xb0, v170
	s_nop 0
	v_ashrrev_i32_e32 v165, 31, v164
	v_lshlrev_b64 v[164:165], 6, v[164:165]
	v_lshl_add_u64 v[164:165], s[10:11], 0, v[164:165]
	v_lshl_add_u64 v[154:155], v[164:165], 0, v[154:155]
	global_store_dwordx4 v[154:155], v[130:133], off
	s_nop 1
	v_pk_add_f32 v[132:133], v[16:17], v[136:137]
	v_pk_add_f32 v[130:131], v[14:15], v[134:135]
	global_store_dwordx4 v[154:155], v[130:133], off offset:16

.LBB0_286:
	s_andn2_b64 vcc, exec, s[30:31]
	s_cbranch_vccnz .LBB0_274
	s_lshl_b32 s0, s55, 8
	s_or_b32 s0, s0, s48
	s_cmp_lt_i32 s55, 2
	v_lshl_add_u32 v132, v163, 3, s0
	s_cselect_b64 vcc, -1, 0
	s_lshl_b32 s0, s28, 8
	s_add_i32 s0, s0, s47
	v_add_u32_e32 v131, s0, v162
	v_cndmask_b32_e32 v130, 1.0, v161, vcc
	v_ashrrev_i32_e32 v133, 31, v132
	v_mov_b32_e32 v134, v131
	v_lshl_add_u64 v[132:133], v[132:133], 1, s[14:15]
	v_pk_mul_f32 v[128:129], v[130:131], v[128:129] op_sel_hi:[0,1]
	v_pk_mul_f32 v[126:127], v[130:131], v[126:127] op_sel_hi:[0,1]
	v_pk_mul_f32 v[136:137], v[130:131], v[124:125] op_sel_hi:[0,1]
	v_pk_mul_f32 v[124:125], v[130:131], v[122:123] op_sel_hi:[0,1]
	v_mad_i64_i32 v[134:135], s[0:1], v134, s54, v[132:133]
	v_cvt_pk_bf16_f32 v122, v126, v127
	v_cvt_pk_bf16_f32 v123, v128, v129
	v_cvt_pk_bf16_f32 v124, v124, v125
	v_cvt_pk_bf16_f32 v125, v136, v137
	global_store_dwordx4 v[134:135], v[122:125], off
	v_pk_mul_f32 v[116:117], v[130:131], v[116:117] op_sel_hi:[0,1]
	v_pk_mul_f32 v[114:115], v[130:131], v[114:115] op_sel_hi:[0,1]
	v_pk_mul_f32 v[122:123], v[130:131], v[108:109] op_sel_hi:[0,1]
	v_pk_mul_f32 v[108:109], v[130:131], v[106:107] op_sel_hi:[0,1]
	v_cvt_pk_bf16_f32 v106, v114, v115
	v_cvt_pk_bf16_f32 v107, v116, v117
	v_cvt_pk_bf16_f32 v108, v108, v109
	v_cvt_pk_bf16_f32 v109, v122, v123
	global_store_dwordx4 v[134:135], v[106:109], off offset:256
	v_pk_mul_f32 v[112:113], v[130:131], v[112:113] op_sel_hi:[0,1]
	v_pk_mul_f32 v[110:111], v[130:131], v[110:111] op_sel_hi:[0,1]
	v_add_u32_e32 v106, 16, v131
	v_pk_mul_f32 v[108:109], v[130:131], v[120:121] op_sel_hi:[0,1]
	v_mad_i64_i32 v[114:115], s[0:1], v106, s54, v[132:133]
	v_pk_mul_f32 v[106:107], v[130:131], v[118:119] op_sel_hi:[0,1]
	v_cvt_pk_bf16_f32 v106, v106, v107
	v_cvt_pk_bf16_f32 v107, v108, v109
	v_cvt_pk_bf16_f32 v108, v110, v111
	v_cvt_pk_bf16_f32 v109, v112, v113
	global_store_dwordx4 v[114:115], v[106:109], off
	v_pk_mul_f32 v[100:101], v[130:131], v[100:101] op_sel_hi:[0,1]
	v_pk_mul_f32 v[98:99], v[130:131], v[98:99] op_sel_hi:[0,1]
	v_pk_mul_f32 v[106:107], v[130:131], v[92:93] op_sel_hi:[0,1]
	v_pk_mul_f32 v[92:93], v[130:131], v[90:91] op_sel_hi:[0,1]
	v_cvt_pk_bf16_f32 v90, v98, v99
	v_cvt_pk_bf16_f32 v91, v100, v101
	v_cvt_pk_bf16_f32 v92, v92, v93
	v_cvt_pk_bf16_f32 v93, v106, v107
	global_store_dwordx4 v[114:115], v[90:93], off offset:256
	v_pk_mul_f32 v[96:97], v[130:131], v[96:97] op_sel_hi:[0,1]
	v_pk_mul_f32 v[94:95], v[130:131], v[94:95] op_sel_hi:[0,1]
	v_add_u32_e32 v90, 32, v131
	v_pk_mul_f32 v[92:93], v[130:131], v[104:105] op_sel_hi:[0,1]
	v_mad_i64_i32 v[98:99], s[0:1], v90, s54, v[132:133]
	v_pk_mul_f32 v[90:91], v[130:131], v[102:103] op_sel_hi:[0,1]
	v_cvt_pk_bf16_f32 v90, v90, v91
	v_cvt_pk_bf16_f32 v91, v92, v93
	v_cvt_pk_bf16_f32 v92, v94, v95
	v_cvt_pk_bf16_f32 v93, v96, v97
	global_store_dwordx4 v[98:99], v[90:93], off
	v_pk_mul_f32 v[84:85], v[130:131], v[84:85] op_sel_hi:[0,1]
	v_pk_mul_f32 v[82:83], v[130:131], v[82:83] op_sel_hi:[0,1]
	v_pk_mul_f32 v[90:91], v[130:131], v[76:77] op_sel_hi:[0,1]
	v_pk_mul_f32 v[76:77], v[130:131], v[74:75] op_sel_hi:[0,1]
	v_cvt_pk_bf16_f32 v74, v82, v83
	v_cvt_pk_bf16_f32 v75, v84, v85
	v_cvt_pk_bf16_f32 v76, v76, v77
	v_cvt_pk_bf16_f32 v77, v90, v91
	global_store_dwordx4 v[98:99], v[74:77], off offset:256
	v_pk_mul_f32 v[80:81], v[130:131], v[80:81] op_sel_hi:[0,1]
	v_pk_mul_f32 v[78:79], v[130:131], v[78:79] op_sel_hi:[0,1]
	v_add_u32_e32 v74, 48, v131
	v_pk_mul_f32 v[76:77], v[130:131], v[88:89] op_sel_hi:[0,1]
	v_mad_i64_i32 v[82:83], s[0:1], v74, s54, v[132:133]
	v_pk_mul_f32 v[74:75], v[130:131], v[86:87] op_sel_hi:[0,1]
	v_cvt_pk_bf16_f32 v74, v74, v75
	v_cvt_pk_bf16_f32 v75, v76, v77
	v_cvt_pk_bf16_f32 v76, v78, v79
	v_cvt_pk_bf16_f32 v77, v80, v81
	global_store_dwordx4 v[82:83], v[74:77], off
	v_pk_mul_f32 v[72:73], v[130:131], v[72:73] op_sel_hi:[0,1]
	v_pk_mul_f32 v[70:71], v[130:131], v[70:71] op_sel_hi:[0,1]
	v_pk_mul_f32 v[74:75], v[130:131], v[68:69] op_sel_hi:[0,1]
	v_pk_mul_f32 v[68:69], v[130:131], v[66:67] op_sel_hi:[0,1]
	v_cvt_pk_bf16_f32 v66, v70, v71
	v_cvt_pk_bf16_f32 v67, v72, v73
	v_cvt_pk_bf16_f32 v68, v68, v69
	v_cvt_pk_bf16_f32 v69, v74, v75
	global_store_dwordx4 v[82:83], v[66:69], off offset:256
	v_pk_mul_f32 v[64:65], v[130:131], v[64:65] op_sel_hi:[0,1]
	v_pk_mul_f32 v[62:63], v[130:131], v[62:63] op_sel_hi:[0,1]
	v_add_u32_e32 v66, 0x80, v131
	v_pk_mul_f32 v[68:69], v[130:131], v[60:61] op_sel_hi:[0,1]
	v_pk_mul_f32 v[60:61], v[130:131], v[58:59] op_sel_hi:[0,1]
	v_mad_i64_i32 v[66:67], s[0:1], v66, s54, v[132:133]
	v_cvt_pk_bf16_f32 v58, v62, v63
	v_cvt_pk_bf16_f32 v59, v64, v65
	v_cvt_pk_bf16_f32 v60, v60, v61
	v_cvt_pk_bf16_f32 v61, v68, v69
	global_store_dwordx4 v[66:67], v[58:61], off
	v_pk_mul_f32 v[52:53], v[130:131], v[52:53] op_sel_hi:[0,1]
	v_pk_mul_f32 v[50:51], v[130:131], v[50:51] op_sel_hi:[0,1]
	v_pk_mul_f32 v[58:59], v[130:131], v[44:45] op_sel_hi:[0,1]
	v_pk_mul_f32 v[44:45], v[130:131], v[42:43] op_sel_hi:[0,1]
	v_cvt_pk_bf16_f32 v42, v50, v51
	v_cvt_pk_bf16_f32 v43, v52, v53
	v_cvt_pk_bf16_f32 v44, v44, v45
	v_cvt_pk_bf16_f32 v45, v58, v59
	global_store_dwordx4 v[66:67], v[42:45], off offset:256
	v_pk_mul_f32 v[48:49], v[130:131], v[48:49] op_sel_hi:[0,1]
	v_pk_mul_f32 v[46:47], v[130:131], v[46:47] op_sel_hi:[0,1]
	v_add_u32_e32 v42, 0x90, v131
	v_pk_mul_f32 v[44:45], v[130:131], v[56:57] op_sel_hi:[0,1]
	v_mad_i64_i32 v[50:51], s[0:1], v42, s54, v[132:133]
	v_pk_mul_f32 v[42:43], v[130:131], v[54:55] op_sel_hi:[0,1]
	v_cvt_pk_bf16_f32 v42, v42, v43
	v_cvt_pk_bf16_f32 v43, v44, v45
	v_cvt_pk_bf16_f32 v44, v46, v47
	v_cvt_pk_bf16_f32 v45, v48, v49
	global_store_dwordx4 v[50:51], v[42:45], off
	v_pk_mul_f32 v[36:37], v[130:131], v[36:37] op_sel_hi:[0,1]
	v_pk_mul_f32 v[34:35], v[130:131], v[34:35] op_sel_hi:[0,1]
	v_pk_mul_f32 v[42:43], v[130:131], v[28:29] op_sel_hi:[0,1]
	v_pk_mul_f32 v[28:29], v[130:131], v[26:27] op_sel_hi:[0,1]
	v_cvt_pk_bf16_f32 v26, v34, v35
	v_cvt_pk_bf16_f32 v27, v36, v37
	v_cvt_pk_bf16_f32 v28, v28, v29
	v_cvt_pk_bf16_f32 v29, v42, v43
	global_store_dwordx4 v[50:51], v[26:29], off offset:256
	v_pk_mul_f32 v[32:33], v[130:131], v[32:33] op_sel_hi:[0,1]
	v_pk_mul_f32 v[30:31], v[130:131], v[30:31] op_sel_hi:[0,1]
	v_add_u32_e32 v26, 0xa0, v131
	v_pk_mul_f32 v[28:29], v[130:131], v[40:41] op_sel_hi:[0,1]
	v_mad_i64_i32 v[34:35], s[0:1], v26, s54, v[132:133]
	v_pk_mul_f32 v[26:27], v[130:131], v[38:39] op_sel_hi:[0,1]
	v_cvt_pk_bf16_f32 v26, v26, v27
	v_cvt_pk_bf16_f32 v27, v28, v29
	v_cvt_pk_bf16_f32 v28, v30, v31
	v_cvt_pk_bf16_f32 v29, v32, v33
	global_store_dwordx4 v[34:35], v[26:29], off
	v_pk_mul_f32 v[20:21], v[130:131], v[20:21] op_sel_hi:[0,1]
	v_pk_mul_f32 v[18:19], v[130:131], v[18:19] op_sel_hi:[0,1]
	v_pk_mul_f32 v[26:27], v[130:131], v[12:13] op_sel_hi:[0,1]
	v_pk_mul_f32 v[12:13], v[130:131], v[10:11] op_sel_hi:[0,1]
	v_cvt_pk_bf16_f32 v10, v18, v19
	v_cvt_pk_bf16_f32 v11, v20, v21
	v_cvt_pk_bf16_f32 v12, v12, v13
	v_cvt_pk_bf16_f32 v13, v26, v27
	global_store_dwordx4 v[34:35], v[10:13], off offset:256
	v_pk_mul_f32 v[16:17], v[130:131], v[16:17] op_sel_hi:[0,1]
	v_pk_mul_f32 v[14:15], v[130:131], v[14:15] op_sel_hi:[0,1]
	v_add_u32_e32 v10, 0xb0, v131
	v_pk_mul_f32 v[12:13], v[130:131], v[24:25] op_sel_hi:[0,1]
	v_mad_i64_i32 v[18:19], s[0:1], v10, s54, v[132:133]
	v_pk_mul_f32 v[10:11], v[130:131], v[22:23] op_sel_hi:[0,1]
	v_cvt_pk_bf16_f32 v10, v10, v11
	v_cvt_pk_bf16_f32 v11, v12, v13
	v_cvt_pk_bf16_f32 v12, v14, v15
	v_cvt_pk_bf16_f32 v13, v16, v17
	global_store_dwordx4 v[18:19], v[10:13], off
	v_pk_mul_f32 v[8:9], v[130:131], v[8:9] op_sel_hi:[0,1]
	v_pk_mul_f32 v[6:7], v[130:131], v[6:7] op_sel_hi:[0,1]
	v_pk_mul_f32 v[10:11], v[130:131], v[4:5] op_sel_hi:[0,1]
	v_pk_mul_f32 v[4:5], v[130:131], v[2:3] op_sel_hi:[0,1]
	v_cvt_pk_bf16_f32 v2, v6, v7
	v_cvt_pk_bf16_f32 v3, v8, v9
	v_cvt_pk_bf16_f32 v4, v4, v5
	v_cvt_pk_bf16_f32 v5, v10, v11
	global_store_dwordx4 v[18:19], v[2:5], off offset:256
	s_branch .LBB0_274

.LBB0_354:
	s_ashr_i32 s23, s22, 31
	s_lshl_b64 s[0:1], s[22:23], 27
	s_add_u32 s34, s48, s0
	s_addc_u32 s35, s49, s1
	s_cmpk_lt_u32 s69, 0x80
	s_cselect_b64 s[20:21], -1, 0
	s_and_b64 s[0:1], s[20:21], exec
	s_cselect_b32 s0, 0, 0x7c0
	v_cndmask_b32_e64 v2, v161, v160, s[20:21]
	s_or_b32 s38, s72, s0
	v_add_u32_e32 v4, s38, v2
	v_mov_b64_e32 v[2:3], s[30:31]
	v_mad_i64_i32 v[4:5], s[0:1], v4, s57, v[2:3]
	s_lshl_b32 s0, s25, 8
	s_mov_b32 s1, s24
	v_lshl_add_u64 v[4:5], v[4:5], 0, s[0:1]
	v_mov_b32_e32 v153, v151
	v_lshl_add_u64 v[4:5], v[4:5], 0, v[152:153]
	s_waitcnt vmcnt(0)
	global_load_dwordx4 v[98:101], v[4:5], off
	global_load_dwordx4 v[102:105], v[4:5], off offset:1024
	v_cndmask_b32_e64 v4, v163, v162, s[20:21]
	v_add_u32_e32 v4, s38, v4
	v_mad_i64_i32 v[4:5], s[22:23], v4, s57, v[2:3]
	v_lshl_add_u64 v[4:5], v[4:5], 0, s[0:1]
	v_lshl_add_u64 v[4:5], v[4:5], 0, v[152:153]
	global_load_dwordx4 v[106:109], v[4:5], off
	global_load_dwordx4 v[110:113], v[4:5], off offset:1024
	v_cndmask_b32_e64 v4, v165, v164, s[20:21]
	v_add_u32_e32 v4, s38, v4
	v_cndmask_b32_e64 v6, v167, v166, s[20:21]
	v_mad_i64_i32 v[4:5], s[22:23], v4, s57, v[2:3]
	s_lshl_b32 s36, s25, 9
	s_mov_b32 s37, s24
	v_add_u32_e32 v6, s38, v6
	v_lshl_add_u64 v[4:5], v[4:5], 0, s[36:37]
	v_mov_b32_e32 v155, v151
	v_mad_i64_i32 v[6:7], s[22:23], v6, s57, v[2:3]
	v_lshl_add_u64 v[4:5], v[4:5], 0, v[154:155]
	v_lshl_add_u64 v[6:7], v[6:7], 0, s[36:37]
	v_lshl_add_u64 v[6:7], v[6:7], 0, v[154:155]
	global_load_dwordx4 v[114:117], v[4:5], off offset:2048
	global_load_dwordx4 v[118:121], v[6:7], off offset:2048
	v_cndmask_b32_e64 v4, v169, v168, s[20:21]
	v_add_u32_e32 v4, s38, v4
	v_cndmask_b32_e64 v6, v171, v170, s[20:21]
	v_mad_i64_i32 v[4:5], s[22:23], v4, s57, v[2:3]
	v_add_u32_e32 v6, s38, v6
	v_lshl_add_u64 v[4:5], v[4:5], 0, s[36:37]
	v_mad_i64_i32 v[2:3], s[22:23], v6, s57, v[2:3]
	v_lshl_add_u64 v[4:5], v[4:5], 0, v[154:155]
	v_lshl_add_u64 v[2:3], v[2:3], 0, s[36:37]
	v_lshl_add_u64 v[2:3], v[2:3], 0, v[154:155]
	global_load_dwordx4 v[122:125], v[4:5], off offset:2048
	global_load_dwordx4 v[126:129], v[2:3], off offset:2048
	s_add_u32 s1, s34, s36
	s_addc_u32 s23, s35, 0
	s_add_u32 s22, s1, s58
	s_addc_u32 s23, s23, 0
	s_add_u32 s34, s30, s0
	s_addc_u32 s35, s31, 0
	s_add_u32 s36, s30, s36
	s_mov_b32 s73, 0
	s_addc_u32 s37, s31, 0
	s_mov_b32 s76, 30
	v_mov_b32_e32 v155, 0
	v_mov_b32_e32 v2, 0
	v_mov_b32_e32 v3, 0
	v_mov_b32_e32 v4, 0
	v_mov_b32_e32 v5, 0
	v_mov_b32_e32 v6, 0
	v_mov_b32_e32 v7, 0
	v_mov_b32_e32 v8, 0
	v_mov_b32_e32 v9, 0
	v_mov_b32_e32 v10, 0
	v_mov_b32_e32 v11, 0
	v_mov_b32_e32 v12, 0
	v_mov_b32_e32 v13, 0
	v_mov_b32_e32 v14, 0
	v_mov_b32_e32 v15, 0
	v_mov_b32_e32 v16, 0
	v_mov_b32_e32 v17, 0
	v_mov_b32_e32 v18, 0
	v_mov_b32_e32 v19, 0
	v_mov_b32_e32 v20, 0
	v_mov_b32_e32 v21, 0
	v_mov_b32_e32 v22, 0
	v_mov_b32_e32 v23, 0
	v_mov_b32_e32 v24, 0
	v_mov_b32_e32 v25, 0
	v_mov_b32_e32 v26, 0
	v_mov_b32_e32 v27, 0
	v_mov_b32_e32 v28, 0
	v_mov_b32_e32 v29, 0
	v_mov_b32_e32 v30, 0
	v_mov_b32_e32 v31, 0
	v_mov_b32_e32 v32, 0
	v_mov_b32_e32 v33, 0
	v_mov_b32_e32 v34, 0
	v_mov_b32_e32 v35, 0
	v_mov_b32_e32 v36, 0
	v_mov_b32_e32 v37, 0
	v_mov_b32_e32 v38, 0
	v_mov_b32_e32 v39, 0
	v_mov_b32_e32 v40, 0
	v_mov_b32_e32 v41, 0
	v_mov_b32_e32 v42, 0
	v_mov_b32_e32 v43, 0
	v_mov_b32_e32 v44, 0
	v_mov_b32_e32 v45, 0
	v_mov_b32_e32 v46, 0
	v_mov_b32_e32 v47, 0
	v_mov_b32_e32 v48, 0
	v_mov_b32_e32 v49, 0
	v_mov_b32_e32 v50, 0
	v_mov_b32_e32 v51, 0
	v_mov_b32_e32 v52, 0
	v_mov_b32_e32 v53, 0
	v_mov_b32_e32 v54, 0
	v_mov_b32_e32 v55, 0
	v_mov_b32_e32 v56, 0
	v_mov_b32_e32 v57, 0
	v_mov_b32_e32 v58, 0
	v_mov_b32_e32 v59, 0
	v_mov_b32_e32 v60, 0
	v_mov_b32_e32 v61, 0
	v_mov_b32_e32 v62, 0
	v_mov_b32_e32 v63, 0
	v_mov_b32_e32 v64, 0
	v_mov_b32_e32 v65, 0
	s_mov_b32 s77, 0
	s_mov_b32 s80, 0
	s_waitcnt lgkmcnt(0)
	s_barrier
	s_branch .LBB0_356

.LBB0_356:
	s_add_i32 s79, s77, 0
	s_add_i32 s0, s79, 0x1c0fc
	v_mov_b32_e32 v72, v156
	v_mov_b32_e32 v66, s0
	ds_read_b32 v67, v66
	v_and_b32_e32 v66, 15, v72
	v_lshlrev_b32_e32 v73, 4, v66
	v_ashrrev_i32_e32 v66, 4, v72
	v_and_b32_e32 v74, 0x70, v72
	v_lshlrev_b32_e32 v68, 8, v66
	v_bitop3_b32 v68, v73, v68, v74 bitop3:0xde
	v_add_u32_e32 v68, 0, v68
	s_waitcnt vmcnt(0)
	ds_write_b128 v68, v[98:101]
	ds_write_b128 v68, v[102:105] offset:16384
	v_lshl_add_u32 v68, v66, 2, s79
	v_add_u32_e32 v68, 0x1a000, v68
	ds_read_b32 v68, v68
	s_waitcnt lgkmcnt(0)
	v_max_f32_e32 v67, v67, v67
	v_max_f32_e32 v185, v155, v155
	v_max_f32_e32 v153, v185, v67
	v_and_b32_e32 v69, 0xffff0000, v102
	s_waitcnt lgkmcnt(0)
	v_sub_f32_e32 v67, v68, v153
	v_mul_f32_e32 v67, 0x3fb8aa3b, v67
	v_exp_f32_e32 v67, v67
	v_lshlrev_b32_e32 v68, 16, v102
	v_and_b32_e32 v70, 0xffff0000, v103
	v_and_b32_e32 v71, 0xffff0000, v104
	v_mul_f32_e32 v68, v67, v68
	v_mul_f32_e32 v69, v67, v69
	v_cvt_pk_bf16_f32 v68, v68, v69
	v_lshlrev_b32_e32 v69, 16, v103
	v_mul_f32_e32 v69, v67, v69
	v_mul_f32_e32 v70, v67, v70
	v_cvt_pk_bf16_f32 v69, v69, v70
	v_lshlrev_b32_e32 v70, 16, v104
	v_mul_f32_e32 v70, v67, v70
	v_mul_f32_e32 v71, v67, v71
	v_cvt_pk_bf16_f32 v70, v70, v71
	v_lshlrev_b32_e32 v71, 16, v105
	v_and_b32_e32 v77, 0xffff0000, v105
	v_mul_f32_e32 v71, v67, v71
	v_mul_f32_e32 v67, v67, v77
	v_cvt_pk_bf16_f32 v71, v71, v67
	v_and_b32_e32 v67, 0xfffff0, v66
	v_lshlrev_b32_e32 v77, 1, v66
	v_and_or_b32 v67, v77, 8, v67
	v_bfe_u32 v75, v72, 2, 2
	v_lshrrev_b32_e32 v77, 1, v66
	v_lshrrev_b32_e32 v67, 1, v67
	v_and_b32_e32 v78, 3, v66
	v_or_b32_e32 v67, v67, v75
	v_and_or_b32 v77, v77, 4, v78
	v_and_b32_e32 v76, 48, v73
	v_lshlrev_b32_e32 v77, 6, v77
	v_lshl_add_u32 v67, v67, 9, 0
	v_add3_u32 v67, v67, v77, v76
	v_add_u32_e32 v77, 0x200, v72
	ds_write_b128 v67, v[68:71] offset:32768
	v_ashrrev_i32_e32 v67, 4, v77
	v_lshlrev_b32_e32 v68, 8, v67
	v_bitop3_b32 v68, v68, v73, v74 bitop3:0xf6
	v_add_u32_e32 v68, 0, v68
	ds_write_b128 v68, v[106:109]
	ds_write_b128 v68, v[110:113] offset:16384
	v_lshl_add_u32 v68, v67, 2, s79
	v_add_u32_e32 v68, 0x1a000, v68
	ds_read_b32 v68, v68
	v_and_b32_e32 v69, 0xffff0000, v110
	v_and_b32_e32 v70, 0xffff0000, v111
	v_and_b32_e32 v73, 0xffff0000, v112
	v_and_b32_e32 v74, 0xffff0000, v113
	s_waitcnt lgkmcnt(0)
	v_sub_f32_e32 v68, v68, v153
	v_mul_f32_e32 v68, 0x3fb8aa3b, v68
	v_exp_f32_e32 v71, v68
	v_lshlrev_b32_e32 v68, 16, v110
	s_add_i32 s78, s80, 1
	s_cmpk_eq_i32 s77, 0x1f00
	v_mul_f32_e32 v68, v71, v68
	v_mul_f32_e32 v69, v71, v69
	v_cvt_pk_bf16_f32 v68, v68, v69
	v_lshlrev_b32_e32 v69, 16, v111
	v_mul_f32_e32 v69, v71, v69
	v_mul_f32_e32 v70, v71, v70
	v_cvt_pk_bf16_f32 v69, v69, v70
	v_lshlrev_b32_e32 v70, 16, v112
	v_mul_f32_e32 v70, v71, v70
	v_mul_f32_e32 v73, v71, v73
	v_cvt_pk_bf16_f32 v70, v70, v73
	v_lshlrev_b32_e32 v73, 16, v113
	v_mul_f32_e32 v73, v71, v73
	v_mul_f32_e32 v71, v71, v74
	v_cvt_pk_bf16_f32 v71, v73, v71
	v_and_b32_e32 v73, 0xfffff0, v67
	v_lshlrev_b32_e32 v74, 1, v67
	v_and_or_b32 v73, v74, 8, v73
	v_lshrrev_b32_e32 v73, 1, v73
	v_lshrrev_b32_e32 v74, 1, v67
	v_or_b32_e32 v73, v73, v75
	v_and_b32_e32 v75, 3, v67
	v_and_or_b32 v74, v74, 4, v75
	v_lshlrev_b32_e32 v74, 6, v74
	v_lshl_add_u32 v73, v73, 9, 0
	v_add3_u32 v73, v73, v74, v76
	ds_write_b128 v73, v[68:71] offset:32768
	v_lshlrev_b32_e32 v69, 4, v72
	v_lshlrev_b32_e32 v68, 10, v72
	v_and_b32_e32 v75, 48, v69
	v_ashrrev_i32_e32 v69, 5, v72
	v_and_b32_e32 v68, 0x4000, v68
	v_and_b32_e32 v70, 0xfffff0, v69
	v_lshlrev_b32_e32 v71, 1, v69
	v_add_u32_e32 v73, 0, v68
	v_lshlrev_b32_e32 v68, 3, v72
	v_and_or_b32 v70, v71, 8, v70
	v_bfe_u32 v74, v68, 5, 2
	v_lshrrev_b32_e32 v71, 1, v69
	v_lshrrev_b32_e32 v70, 1, v70
	v_and_b32_e32 v76, 3, v69
	v_or_b32_e32 v70, v70, v74
	v_and_or_b32 v71, v71, 4, v76
	v_lshlrev_b32_e32 v71, 6, v71
	v_lshl_add_u32 v70, v70, 9, v73
	v_add3_u32 v70, v70, v71, v75
	ds_write_b128 v70, v[114:117] offset:49152
	v_ashrrev_i32_e32 v70, 5, v77
	v_and_b32_e32 v71, 0xfffff0, v70
	v_lshlrev_b32_e32 v76, 1, v70
	v_and_or_b32 v71, v76, 8, v71
	v_lshrrev_b32_e32 v76, 1, v70
	v_lshrrev_b32_e32 v71, 1, v71
	v_and_b32_e32 v77, 3, v70
	v_or_b32_e32 v71, v71, v74
	v_and_or_b32 v76, v76, 4, v77
	v_lshlrev_b32_e32 v76, 6, v76
	v_lshl_add_u32 v71, v71, 9, v73
	v_add3_u32 v71, v71, v76, v75
	ds_write_b128 v71, v[118:121] offset:49152
	v_add_u32_e32 v71, 0x400, v72
	v_ashrrev_i32_e32 v71, 5, v71
	v_and_b32_e32 v76, 0xfffff0, v71
	v_lshlrev_b32_e32 v77, 1, v71
	v_and_or_b32 v76, v77, 8, v76
	v_lshrrev_b32_e32 v77, 1, v71
	v_lshrrev_b32_e32 v76, 1, v76
	v_and_b32_e32 v78, 3, v71
	v_or_b32_e32 v76, v76, v74
	v_and_or_b32 v77, v77, 4, v78
	v_lshlrev_b32_e32 v77, 6, v77
	v_lshl_add_u32 v76, v76, 9, v73
	v_add_u32_e32 v72, 0x600, v72
	v_add3_u32 v76, v76, v77, v75
	v_ashrrev_i32_e32 v72, 5, v72
	ds_write_b128 v76, v[122:125] offset:49152
	v_and_b32_e32 v76, 0xfffff0, v72
	v_lshlrev_b32_e32 v77, 1, v72
	v_and_or_b32 v76, v77, 8, v76
	v_lshrrev_b32_e32 v76, 1, v76
	v_lshrrev_b32_e32 v77, 1, v72
	v_or_b32_e32 v74, v76, v74
	v_and_b32_e32 v76, 3, v72
	v_and_or_b32 v76, v77, 4, v76
	v_lshlrev_b32_e32 v76, 6, v76
	v_lshl_add_u32 v73, v74, 9, v73
	v_add3_u32 v73, v73, v76, v75
	ds_write_b128 v73, v[126:129] offset:49152
	s_cbranch_scc1 .LBB0_358
	s_and_b64 s[0:1], s[20:21], exec
	s_cselect_b32 s0, s78, s76
	s_lshl_b32 s0, s0, 6
	v_sub_u32_e32 v74, 63, v66
	v_cndmask_b32_e64 v66, v74, v66, s[20:21]
	s_add_i32 s25, s0, s72
	v_add_u32_e32 v66, s25, v66
	v_mov_b64_e32 v[74:75], s[34:35]
	v_mad_i64_i32 v[76:77], s[0:1], v66, s57, v[74:75]
	v_sub_u32_e32 v66, 63, v67
	v_cndmask_b32_e64 v66, v66, v67, s[20:21]
	v_and_b32_e32 v73, 0x78, v68
	v_add_u32_e32 v66, s25, v66
	v_lshlrev_b32_e32 v150, 1, v73
	v_mad_i64_i32 v[66:67], s[0:1], v66, s57, v[74:75]
	v_lshl_add_u64 v[76:77], v[76:77], 0, v[150:151]
	v_lshl_add_u64 v[66:67], v[66:67], 0, v[150:151]
	global_load_dwordx4 v[98:101], v[76:77], off
	global_load_dwordx4 v[102:105], v[76:77], off offset:1024
	global_load_dwordx4 v[106:109], v[66:67], off
	global_load_dwordx4 v[110:113], v[66:67], off offset:1024
	v_sub_u32_e32 v66, 63, v69
	v_cndmask_b32_e64 v66, v66, v69, s[20:21]
	v_sub_u32_e32 v73, 63, v70
	v_add_u32_e32 v69, s25, v66
	v_mov_b64_e32 v[66:67], s[36:37]
	v_and_b32_e32 v68, 0xf8, v68
	v_cndmask_b32_e64 v70, v73, v70, s[20:21]
	v_mad_i64_i32 v[74:75], s[0:1], v69, s57, v[66:67]
	v_lshlrev_b32_e32 v150, 1, v68
	v_add_u32_e32 v70, s25, v70
	v_lshl_add_u64 v[68:69], v[74:75], 0, v[150:151]
	v_mad_i64_i32 v[74:75], s[0:1], v70, s57, v[66:67]
	v_lshl_add_u64 v[74:75], v[74:75], 0, v[150:151]
	global_load_dwordx4 v[114:117], v[68:69], off offset:2048
	global_load_dwordx4 v[118:121], v[74:75], off offset:2048
	v_sub_u32_e32 v68, 63, v71
	v_cndmask_b32_e64 v68, v68, v71, s[20:21]
	v_sub_u32_e32 v70, 63, v72
	v_add_u32_e32 v68, s25, v68
	v_cndmask_b32_e64 v70, v70, v72, s[20:21]
	v_mad_i64_i32 v[68:69], s[0:1], v68, s57, v[66:67]
	v_add_u32_e32 v70, s25, v70
	v_lshl_add_u64 v[68:69], v[68:69], 0, v[150:151]
	v_mad_i64_i32 v[66:67], s[0:1], v70, s57, v[66:67]
	v_lshl_add_u64 v[66:67], v[66:67], 0, v[150:151]
	global_load_dwordx4 v[122:125], v[68:69], off offset:2048
	global_load_dwordx4 v[126:129], v[66:67], off offset:2048

.LBB0_426:
	s_lshl_b32 s0, s27, 8
	s_add_i32 s0, s0, s97
	s_ashr_i32 s1, s0, 31
	s_add_i32 s8, s0, 8
	s_lshl_b64 s[10:11], s[0:1], 11
	s_ashr_i32 s9, s8, 31
	v_lshl_add_u64 v[76:77], v[68:69], 0, s[10:11]
	v_lshl_add_u64 v[78:79], v[70:71], 0, s[10:11]
	v_mad_i64_i32 v[80:81], s[10:11], s0, v86, v[72:73]
	s_lshl_b64 s[10:11], s[8:9], 11
	global_load_dwordx4 v[2:5], v[66:67], off
	global_load_dwordx4 v[6:9], v[66:67], off offset:16
	global_load_dwordx4 v[10:13], v[66:67], off offset:2048
	global_load_dwordx4 v[14:17], v[66:67], off offset:2064
	v_lshl_add_u64 v[82:83], v[68:69], 0, s[10:11]
	v_lshl_add_u64 v[84:85], v[70:71], 0, s[10:11]
	v_mad_i64_i32 v[90:91], s[8:9], s8, v86, v[72:73]
	global_load_dwordx4 v[58:61], v[76:77], off
	global_load_dwordx4 v[22:25], v[76:77], off offset:1024
	global_load_dwordx4 v[54:57], v[78:79], off
	global_load_dwordx4 v[18:21], v[78:79], off offset:1024
	global_load_dwordx4 v[62:65], v[80:81], off
	global_load_dwordx4 v[26:29], v[80:81], off offset:1024
	s_waitcnt vmcnt(0) lgkmcnt(0)
	global_load_dwordx4 v[42:45], v[82:83], off
	global_load_dwordx4 v[38:41], v[82:83], off offset:1024
	global_load_dwordx4 v[50:53], v[84:85], off
	global_load_dwordx4 v[46:49], v[84:85], off offset:1024
	global_load_dwordx4 v[30:33], v[90:91], off
	global_load_dwordx4 v[34:37], v[90:91], off offset:1024
	s_add_i32 s28, s0, 16
	s_mov_b32 s14, s4
	s_mov_b32 s29, 0
.LBB0_427:
	s_min_u32 s8, s29, 29
	s_ashr_i32 s15, s14, 31
	s_waitcnt vmcnt(0) lgkmcnt(0)
	v_lshlrev_b32_e32 v89, 16, v62
	v_and_b32_e32 v98, 0xffff0000, v62
	v_lshlrev_b32_e32 v99, 16, v63
	v_and_b32_e32 v100, 0xffff0000, v63
	v_lshlrev_b32_e32 v101, 16, v64
	v_and_b32_e32 v102, 0xffff0000, v64
	v_lshlrev_b32_e32 v103, 16, v65
	v_and_b32_e32 v104, 0xffff0000, v65
	v_lshlrev_b32_e32 v76, 16, v61
	v_and_b32_e32 v77, 0xffff0000, v61
	v_lshlrev_b32_e32 v78, 16, v57
	v_and_b32_e32 v79, 0xffff0000, v57
	v_lshlrev_b32_e32 v80, 16, v60
	v_and_b32_e32 v81, 0xffff0000, v60
	v_lshlrev_b32_e32 v60, 16, v56
	v_and_b32_e32 v61, 0xffff0000, v56
	v_lshlrev_b32_e32 v56, 16, v59
	v_and_b32_e32 v57, 0xffff0000, v59
	v_lshlrev_b32_e32 v82, 16, v55
	v_and_b32_e32 v83, 0xffff0000, v55
	v_lshlrev_b32_e32 v84, 16, v58
	v_and_b32_e32 v85, 0xffff0000, v58
	v_lshlrev_b32_e32 v58, 16, v54
	v_and_b32_e32 v59, 0xffff0000, v54
	v_lshlrev_b32_e32 v105, 16, v26
	v_and_b32_e32 v106, 0xffff0000, v26
	v_lshlrev_b32_e32 v107, 16, v27
	v_and_b32_e32 v108, 0xffff0000, v27
	v_lshlrev_b32_e32 v109, 16, v28
	v_and_b32_e32 v110, 0xffff0000, v28
	v_lshlrev_b32_e32 v111, 16, v29
	v_and_b32_e32 v112, 0xffff0000, v29
	v_lshlrev_b32_e32 v54, 16, v25
	v_and_b32_e32 v55, 0xffff0000, v25
	v_lshlrev_b32_e32 v90, 16, v21
	v_and_b32_e32 v91, 0xffff0000, v21
	v_lshlrev_b32_e32 v92, 16, v24
	v_and_b32_e32 v93, 0xffff0000, v24
	v_lshlrev_b32_e32 v24, 16, v20
	v_and_b32_e32 v25, 0xffff0000, v20
	v_lshlrev_b32_e32 v20, 16, v23
	v_and_b32_e32 v21, 0xffff0000, v23
	v_lshlrev_b32_e32 v94, 16, v19
	v_and_b32_e32 v95, 0xffff0000, v19
	v_lshlrev_b32_e32 v96, 16, v22
	v_and_b32_e32 v97, 0xffff0000, v22
	v_lshlrev_b32_e32 v22, 16, v18
	v_and_b32_e32 v23, 0xffff0000, v18
	v_mov_b64_e32 v[26:27], v[34:35]
	v_mov_b64_e32 v[64:65], v[32:33]
	s_lshl_b32 s8, s8, 3
	v_mov_b64_e32 v[28:29], v[36:37]
	v_mov_b64_e32 v[62:63], v[30:31]
	s_lshl_b64 s[0:1], s[14:15], 11
	v_mul_f32_e32 v30, 0xbfb8aa3b, v89
	v_mul_f32_e32 v31, 0xbfb8aa3b, v98
	v_mul_f32_e32 v32, 0xbfb8aa3b, v99
	v_mul_f32_e32 v33, 0xbfb8aa3b, v100
	v_mul_f32_e32 v34, 0xbfb8aa3b, v101
	v_mul_f32_e32 v35, 0xbfb8aa3b, v102
	v_mul_f32_e32 v36, 0xbfb8aa3b, v103
	v_mul_f32_e32 v37, 0xbfb8aa3b, v104
	v_pk_add_f32 v[76:77], v[78:79], v[76:77]
	v_pk_add_f32 v[78:79], v[60:61], v[80:81]
	v_pk_add_f32 v[80:81], v[82:83], v[56:57]
	v_pk_add_f32 v[82:83], v[58:59], v[84:85]
	v_pk_add_f32 v[84:85], v[90:91], v[54:55]
	v_pk_add_f32 v[90:91], v[24:25], v[92:93]
	v_pk_add_f32 v[92:93], v[94:95], v[20:21]
	v_pk_add_f32 v[94:95], v[22:23], v[96:97]
	v_mov_b64_e32 v[18:19], v[46:47]
	v_mov_b64_e32 v[60:61], v[44:45]
	v_mov_b64_e32 v[22:23], v[38:39]
	s_add_i32 s8, s28, s8
	v_mul_f32_e32 v89, 0xbfb8aa3b, v105
	v_mul_f32_e32 v98, 0xbfb8aa3b, v106
	v_mul_f32_e32 v99, 0xbfb8aa3b, v107
	v_mul_f32_e32 v100, 0xbfb8aa3b, v108
	v_mul_f32_e32 v101, 0xbfb8aa3b, v109
	v_mul_f32_e32 v102, 0xbfb8aa3b, v110
	v_mul_f32_e32 v103, 0xbfb8aa3b, v111
	v_mul_f32_e32 v104, 0xbfb8aa3b, v112
	v_mov_b64_e32 v[56:57], v[52:53]
	v_mov_b64_e32 v[20:21], v[48:49]
	v_mov_b64_e32 v[58:59], v[42:43]
	v_mov_b64_e32 v[24:25], v[40:41]
	v_exp_f32_e32 v105, v30
	v_exp_f32_e32 v106, v31
	v_exp_f32_e32 v107, v32
	v_exp_f32_e32 v108, v33
	v_exp_f32_e32 v109, v34
	v_exp_f32_e32 v110, v35
	v_exp_f32_e32 v111, v36
	v_exp_f32_e32 v112, v37
	v_mov_b32_e32 v30, v80
	v_mov_b32_e32 v31, v76
	v_mov_b32_e32 v32, v81
	v_mov_b32_e32 v33, v77
	v_mov_b32_e32 v34, v82
	v_mov_b32_e32 v35, v78
	v_mov_b32_e32 v36, v83
	v_mov_b32_e32 v37, v79
	v_lshl_add_u64 v[96:97], v[74:75], 0, s[0:1]
	v_mov_b32_e32 v38, v92
	v_mov_b32_e32 v39, v84
	v_mov_b32_e32 v40, v93
	v_mov_b32_e32 v41, v85
	v_mov_b32_e32 v42, v94
	v_mov_b32_e32 v43, v90
	v_mov_b32_e32 v44, v95
	v_mov_b32_e32 v45, v91
	s_ashr_i32 s9, s8, 31
	v_mad_i64_i32 v[46:47], s[0:1], s8, v86, v[72:73]
	v_mov_b64_e32 v[54:55], v[50:51]
	v_pk_add_f32 v[48:49], v[30:31], v[32:33]
	v_pk_add_f32 v[50:51], v[34:35], v[36:37]
	v_pk_add_f32 v[38:39], v[38:39], v[40:41]
	v_pk_add_f32 v[40:41], v[42:43], v[44:45]
	s_lshl_b64 s[0:1], s[8:9], 11
	global_load_dwordx4 v[30:33], v[46:47], off
	global_load_dwordx4 v[34:37], v[46:47], off offset:1024
	v_pk_add_f32 v[42:43], v[50:51], v[48:49]
	v_pk_add_f32 v[38:39], v[40:41], v[38:39]
	v_lshl_add_u64 v[40:41], v[68:69], 0, s[0:1]
	v_lshl_add_u64 v[46:47], v[70:71], 0, s[0:1]
	v_add_f32_e32 v113, v42, v43
	v_add_f32_e32 v114, v38, v39
	global_load_dwordx4 v[42:45], v[40:41], off
	s_nop 0
	global_load_dwordx4 v[38:41], v[40:41], off offset:1024
	s_nop 0
	global_load_dwordx4 v[50:53], v[46:47], off
	s_nop 0
	global_load_dwordx4 v[46:49], v[46:47], off offset:1024
	v_exp_f32_e32 v89, v89
	v_exp_f32_e32 v99, v99
	v_add_f32_dpp v113, v113, v113 quad_perm:[1,0,3,2] row_mask:0xf bank_mask:0xf bound_ctrl:1
	v_exp_f32_e32 v98, v98
	v_add_f32_e32 v106, 1.0, v106
	v_add_f32_e32 v89, 1.0, v89
	v_add_f32_dpp v114, v114, v114 quad_perm:[1,0,3,2] row_mask:0xf bank_mask:0xf bound_ctrl:1
	v_add_f32_dpp v122, v113, v113 quad_perm:[2,3,0,1] row_mask:0xf bank_mask:0xf bound_ctrl:1
	v_exp_f32_e32 v100, v100
	v_exp_f32_e32 v101, v101
	v_add_f32_e32 v116, 1.0, v99
	v_rcp_f32_e32 v99, v106
	v_rcp_f32_e32 v106, v89
	v_add_f32_dpp v89, v114, v114 quad_perm:[2,3,0,1] row_mask:0xf bank_mask:0xf bound_ctrl:1
	v_add_f32_dpp v114, v122, v122 row_half_mirror row_mask:0xf bank_mask:0xf bound_ctrl:1
	v_add_f32_e32 v107, 1.0, v107
	v_add_f32_dpp v89, v89, v89 row_half_mirror row_mask:0xf bank_mask:0xf bound_ctrl:1
	v_add_f32_dpp v114, v114, v114 row_mirror row_mask:0xf bank_mask:0xf bound_ctrl:1
	v_add_f32_e32 v108, 1.0, v108
	v_add_f32_dpp v89, v89, v89 row_mirror row_mask:0xf bank_mask:0xf bound_ctrl:1
	v_readlane_b32 s1, v114, 16
	v_readlane_b32 s9, v114, 48
	v_add_f32_e32 v115, 1.0, v98
	v_readlane_b32 s0, v114, 0
	v_readlane_b32 s8, v114, 32
	v_readlane_b32 s10, v89, 0
	v_readlane_b32 s11, v89, 16
	v_readlane_b32 s12, v89, 32
	v_readlane_b32 s13, v89, 48
	v_mov_b32_e32 v89, s1
	v_mov_b32_e32 v114, s9
	v_add_f32_e32 v117, 1.0, v100
	v_add_f32_e32 v118, 1.0, v101
	v_rcp_f32_e32 v100, v107
	v_rcp_f32_e32 v101, v108
	v_rcp_f32_e32 v107, v115
	v_rcp_f32_e32 v108, v116
	v_mov_b32_e32 v115, s11
	v_mov_b32_e32 v116, s13
	v_add_f32_e32 v89, s0, v89
	v_add_f32_e32 v114, s8, v114
	v_exp_f32_e32 v102, v102
	v_add_f32_e32 v115, s10, v115
	v_add_f32_e32 v116, s12, v116
	v_cndmask_b32_e64 v89, v89, v114, s[6:7]
	v_cndmask_b32_e64 v115, v115, v116, s[6:7]
	v_mul_f32_e32 v114, 0x3b800000, v89
	v_exp_f32_e32 v103, v103
	v_exp_f32_e32 v104, v104
	v_mul_f32_e32 v116, 0x3b800000, v115
	v_pk_add_f32 v[82:83], v[82:83], v[114:115] op_sel_hi:[1,0] neg_lo:[0,1] neg_hi:[0,1]
	v_add_f32_e32 v109, 1.0, v109
	v_pk_add_f32 v[80:81], v[80:81], v[114:115] op_sel_hi:[1,0] neg_lo:[0,1] neg_hi:[0,1]
	v_pk_add_f32 v[78:79], v[78:79], v[114:115] op_sel_hi:[1,0] neg_lo:[0,1] neg_hi:[0,1]
	v_pk_add_f32 v[76:77], v[76:77], v[114:115] op_sel_hi:[1,0] neg_lo:[0,1] neg_hi:[0,1]
	v_pk_add_f32 v[94:95], v[94:95], v[116:117] op_sel_hi:[1,0] neg_lo:[0,1] neg_hi:[0,1]
	v_pk_mul_f32 v[114:115], v[82:83], v[82:83]
	v_add_f32_e32 v119, 1.0, v102
	v_rcp_f32_e32 v102, v109
	v_rcp_f32_e32 v109, v117
	v_pk_add_f32 v[92:93], v[92:93], v[116:117] op_sel_hi:[1,0] neg_lo:[0,1] neg_hi:[0,1]
	v_pk_add_f32 v[90:91], v[90:91], v[116:117] op_sel_hi:[1,0] neg_lo:[0,1] neg_hi:[0,1]
	v_pk_add_f32 v[84:85], v[84:85], v[116:117] op_sel_hi:[1,0] neg_lo:[0,1] neg_hi:[0,1]
	v_pk_mul_f32 v[116:117], v[80:81], v[80:81]
	v_pk_mul_f32 v[122:123], v[94:95], v[94:95]
	v_add_f32_e32 v89, v114, v115
	v_add_f32_e32 v110, 1.0, v110
	v_add_f32_e32 v111, 1.0, v111
	v_pk_mul_f32 v[124:125], v[92:93], v[92:93]
	v_add_f32_e32 v114, v122, v123
	v_add_f32_e32 v89, v116, v89
	v_add_f32_e32 v120, 1.0, v103
	v_add_f32_e32 v121, 1.0, v104
	v_rcp_f32_e32 v103, v110
	v_rcp_f32_e32 v104, v111
	v_rcp_f32_e32 v110, v118
	v_rcp_f32_e32 v111, v119
	v_pk_mul_f32 v[118:119], v[78:79], v[78:79]
	v_add_f32_e32 v114, v124, v114
	v_add_f32_e32 v89, v117, v89
	v_add_f32_e32 v105, 1.0, v105
	v_add_f32_e32 v112, 1.0, v112
	v_pk_mul_f32 v[126:127], v[90:91], v[90:91]
	v_add_f32_e32 v114, v125, v114
	v_add_f32_e32 v89, v118, v89
	v_rcp_f32_e32 v98, v105
	v_rcp_f32_e32 v105, v112
	v_rcp_f32_e32 v112, v120
	v_rcp_f32_e32 v113, v121
	v_pk_mul_f32 v[120:121], v[76:77], v[76:77]
	v_add_f32_e32 v114, v126, v114
	v_add_f32_e32 v89, v119, v89
	v_pk_mul_f32 v[128:129], v[84:85], v[84:85]
	v_add_f32_e32 v114, v127, v114
	v_add_f32_e32 v89, v120, v89
	v_add_f32_e32 v114, v128, v114
	v_add_f32_e32 v89, v121, v89
	v_add_f32_e32 v114, v129, v114
	s_add_i32 s29, s29, 1
	v_add_f32_dpp v89, v89, v89 quad_perm:[1,0,3,2] row_mask:0xf bank_mask:0xf bound_ctrl:1
	v_add_f32_dpp v114, v114, v114 quad_perm:[1,0,3,2] row_mask:0xf bank_mask:0xf bound_ctrl:1
	s_add_i32 s14, s14, 8
	v_add_f32_dpp v89, v89, v89 quad_perm:[2,3,0,1] row_mask:0xf bank_mask:0xf bound_ctrl:1
	v_add_f32_dpp v114, v114, v114 quad_perm:[2,3,0,1] row_mask:0xf bank_mask:0xf bound_ctrl:1
	s_cmp_lg_u32 s29, 32
	v_add_f32_dpp v89, v89, v89 row_half_mirror row_mask:0xf bank_mask:0xf bound_ctrl:1
	v_add_f32_dpp v114, v114, v114 row_half_mirror row_mask:0xf bank_mask:0xf bound_ctrl:1
	s_nop 0
	v_add_f32_dpp v89, v89, v89 row_mirror row_mask:0xf bank_mask:0xf bound_ctrl:1
	v_add_f32_dpp v114, v114, v114 row_mirror row_mask:0xf bank_mask:0xf bound_ctrl:1
	v_readlane_b32 s1, v89, 16
	v_readlane_b32 s9, v89, 48
	v_readlane_b32 s0, v89, 0
	v_readlane_b32 s8, v89, 32
	v_readlane_b32 s10, v114, 0
	v_readlane_b32 s11, v114, 16
	v_readlane_b32 s12, v114, 32
	v_readlane_b32 s13, v114, 48
	v_mov_b32_e32 v89, s1
	v_mov_b32_e32 v114, s9
	v_mov_b32_e32 v115, s11
	v_mov_b32_e32 v116, s13
	v_add_f32_e32 v89, s0, v89
	v_add_f32_e32 v114, s8, v114
	v_add_f32_e32 v115, s10, v115
	v_add_f32_e32 v116, s12, v116
	v_cndmask_b32_e64 v89, v89, v114, s[6:7]
	v_cndmask_b32_e64 v114, v115, v116, s[6:7]
	v_fmamk_f32 v89, v89, 0x3b800000, v87
	v_fmamk_f32 v114, v114, 0x3b800000, v87
	v_mul_f32_e32 v115, 0x4f800000, v89
	v_cmp_gt_f32_e64 s[8:9], s26, v89
	v_mul_f32_e32 v116, 0x4f800000, v114
	v_cmp_gt_f32_e32 vcc, s26, v114
	v_cndmask_b32_e64 v89, v89, v115, s[8:9]
	v_sqrt_f32_e32 v115, v89
	v_cndmask_b32_e32 v114, v114, v116, vcc
	v_sqrt_f32_e32 v116, v114
	v_add_u32_e32 v117, -1, v115
	v_add_u32_e32 v118, 1, v115
	v_add_u32_e32 v119, -1, v116
	v_fma_f32 v121, -v117, v115, v89
	v_add_u32_e32 v120, 1, v116
	v_fma_f32 v122, -v118, v115, v89
	v_fma_f32 v123, -v119, v116, v114
	v_cmp_ge_f32_e64 s[10:11], 0, v121
	v_fma_f32 v124, -v120, v116, v114
	v_cmp_lt_f32_e64 s[12:13], 0, v122
	v_cndmask_b32_e64 v115, v115, v117, s[10:11]
	v_cmp_ge_f32_e64 s[10:11], 0, v123
	v_cndmask_b32_e64 v115, v115, v118, s[12:13]
	v_mul_f32_e32 v117, 0x37800000, v115
	v_cndmask_b32_e64 v116, v116, v119, s[10:11]
	v_cmp_lt_f32_e64 s[10:11], 0, v124
	v_cndmask_b32_e64 v115, v115, v117, s[8:9]
	v_cmp_class_f32_e64 s[8:9], v89, v88
	v_cndmask_b32_e64 v116, v116, v120, s[10:11]
	v_mul_f32_e32 v118, 0x37800000, v116
	v_cndmask_b32_e32 v116, v116, v118, vcc
	v_cmp_class_f32_e32 vcc, v114, v88
	v_cndmask_b32_e64 v89, v115, v89, s[8:9]
	s_nop 0
	v_cndmask_b32_e32 v115, v116, v114, vcc
	v_div_scale_f32 v114, s[0:1], v89, v89, 1.0
	v_div_scale_f32 v117, s[0:1], v115, v115, 1.0
	v_rcp_f32_e32 v119, v114
	v_rcp_f32_e32 v120, v117
	v_div_scale_f32 v116, vcc, 1.0, v89, 1.0
	v_fma_f32 v121, -v114, v119, 1.0
	v_fma_f32 v122, -v117, v120, 1.0
	v_fmac_f32_e32 v119, v121, v119
	v_div_scale_f32 v118, s[8:9], 1.0, v115, 1.0
	v_fmac_f32_e32 v120, v122, v120
	v_mul_f32_e32 v121, v116, v119
	v_mul_f32_e32 v122, v118, v120
	v_fma_f32 v123, -v114, v121, v116
	v_fma_f32 v124, -v117, v122, v118
	v_fmac_f32_e32 v121, v123, v119
	v_fmac_f32_e32 v122, v124, v120
	v_fma_f32 v114, -v114, v121, v116
	v_fma_f32 v116, -v117, v122, v118
	v_div_fmas_f32 v114, v114, v119, v121
	s_mov_b64 vcc, s[8:9]
	v_div_fixup_f32 v114, v114, v89, 1.0
	v_div_fmas_f32 v89, v116, v120, v122
	v_pk_mul_f32 v[82:83], v[82:83], v[114:115] op_sel_hi:[1,0]
	v_pk_mul_f32 v[80:81], v[80:81], v[114:115] op_sel_hi:[1,0]
	v_pk_mul_f32 v[78:79], v[78:79], v[114:115] op_sel_hi:[1,0]
	v_pk_mul_f32 v[76:77], v[76:77], v[114:115] op_sel_hi:[1,0]
	v_div_fixup_f32 v114, v89, v115, 1.0
	v_pk_mul_f32 v[82:83], v[2:3], v[82:83]
	v_pk_mul_f32 v[80:81], v[4:5], v[80:81]
	v_pk_mul_f32 v[78:79], v[6:7], v[78:79]
	v_pk_mul_f32 v[76:77], v[8:9], v[76:77]
	v_pk_mul_f32 v[94:95], v[94:95], v[114:115] op_sel_hi:[1,0]
	v_pk_mul_f32 v[92:93], v[92:93], v[114:115] op_sel_hi:[1,0]
	v_pk_mul_f32 v[90:91], v[90:91], v[114:115] op_sel_hi:[1,0]
	v_pk_mul_f32 v[84:85], v[84:85], v[114:115] op_sel_hi:[1,0]
	v_pk_mul_f32 v[82:83], v[98:99], v[82:83]
	v_pk_mul_f32 v[80:81], v[100:101], v[80:81]
	v_pk_mul_f32 v[78:79], v[102:103], v[78:79]
	v_pk_mul_f32 v[98:99], v[104:105], v[76:77]
	v_pk_mul_f32 v[94:95], v[10:11], v[94:95]
	v_pk_mul_f32 v[92:93], v[12:13], v[92:93]
	v_pk_mul_f32 v[90:91], v[14:15], v[90:91]
	v_pk_mul_f32 v[84:85], v[16:17], v[84:85]
	v_cvt_pk_bf16_f32 v76, v82, v83
	v_cvt_pk_bf16_f32 v77, v80, v81
	v_cvt_pk_bf16_f32 v78, v78, v79
	v_cvt_pk_bf16_f32 v79, v98, v99
	v_pk_mul_f32 v[80:81], v[106:107], v[94:95]
	v_pk_mul_f32 v[82:83], v[108:109], v[92:93]
	v_pk_mul_f32 v[90:91], v[110:111], v[90:91]
	v_pk_mul_f32 v[84:85], v[112:113], v[84:85]
	global_store_dwordx4 v[96:97], v[76:79], off
	s_nop 1
	v_cvt_pk_bf16_f32 v76, v80, v81
	v_cvt_pk_bf16_f32 v77, v82, v83
	v_cvt_pk_bf16_f32 v78, v90, v91
	v_cvt_pk_bf16_f32 v79, v84, v85
	global_store_dwordx4 v[96:97], v[76:79], off offset:1024
	s_cbranch_scc1 .LBB0_427
	s_add_i32 s27, s27, s74
	s_add_i32 s4, s4, s5
	s_cmpk_gt_i32 s27, 0xff
	s_cbranch_scc0 .LBB0_426

.LBB0_434:
	ds_read_b128 v[146:149], v152
	ds_read_b128 v[156:159], v152 offset:1024
	ds_read_b128 v[160:163], v152 offset:2048
	ds_read_b128 v[164:167], v152 offset:3072
	s_add_u32 s0, s36, 0xfffc0080
	s_addc_u32 s1, s37, -1
	s_cmp_eq_u32 s69, 12
	s_cselect_b32 s41, s60, s1
	s_cselect_b32 s40, s61, s0
	s_cselect_b32 s39, s62, s67
	s_cselect_b32 s38, s63, s66
	s_mov_b32 m0, s50
	v_lshl_add_u64 v[200:201], s[36:37], 0, v[144:145]
	ds_read_b128 v[168:171], v153
	ds_read_b128 v[172:175], v153 offset:1024
	ds_read_b128 v[176:179], v153 offset:2048
	ds_read_b128 v[180:183], v153 offset:3072
	ds_read_b128 v[184:187], v153 offset:4096
	ds_read_b128 v[188:191], v153 offset:5120
	ds_read_b128 v[192:195], v153 offset:6144
	ds_read_b128 v[196:199], v153 offset:7168
	global_load_lds_dwordx4 v[200:201], off
	v_lshl_add_u64 v[200:201], s[36:37], 0, v[142:143]
	s_mov_b32 m0, s51
	s_nop 0
	global_load_lds_dwordx4 v[200:201], off
	s_waitcnt lgkmcnt(8)
	s_waitcnt vmcnt(10)
	s_barrier
	s_waitcnt lgkmcnt(0)
	s_waitcnt lgkmcnt(0)
	v_mfma_f32_16x16x32_bf16 v[126:129], v[146:149], v[168:171], v[126:129]
	v_mfma_f32_16x16x32_bf16 v[122:125], v[160:163], v[168:171], v[122:125]
	v_mfma_f32_16x16x32_bf16 v[114:117], v[146:149], v[176:179], v[114:117]
	v_mfma_f32_16x16x32_bf16 v[106:109], v[160:163], v[176:179], v[106:109]
	v_mfma_f32_16x16x32_bf16 v[98:101], v[146:149], v[184:187], v[98:101]
	v_mfma_f32_16x16x32_bf16 v[90:93], v[160:163], v[184:187], v[90:93]
	v_mfma_f32_16x16x32_bf16 v[82:85], v[146:149], v[192:195], v[82:85]
	v_mfma_f32_16x16x32_bf16 v[74:77], v[160:163], v[192:195], v[74:77]
	v_mfma_f32_16x16x32_bf16 v[126:129], v[156:159], v[172:175], v[126:129]
	v_mfma_f32_16x16x32_bf16 v[122:125], v[164:167], v[172:175], v[122:125]
	v_mfma_f32_16x16x32_bf16 v[114:117], v[156:159], v[180:183], v[114:117]
	v_mfma_f32_16x16x32_bf16 v[106:109], v[164:167], v[180:183], v[106:109]
	v_mfma_f32_16x16x32_bf16 v[98:101], v[156:159], v[188:191], v[98:101]
	v_mfma_f32_16x16x32_bf16 v[90:93], v[164:167], v[188:191], v[90:93]
	v_mfma_f32_16x16x32_bf16 v[82:85], v[156:159], v[196:199], v[82:85]
	v_mfma_f32_16x16x32_bf16 v[74:77], v[164:167], v[196:199], v[74:77]
	s_barrier
	s_mov_b32 m0, s52
	v_lshl_add_u64 v[216:217], s[38:39], 0, v[138:139]
	ds_read_b128 v[200:203], v154
	ds_read_b128 v[204:207], v154 offset:1024
	ds_read_b128 v[208:211], v154 offset:2048
	ds_read_b128 v[212:215], v154 offset:3072
	global_load_lds_dwordx4 v[216:217], off
	v_lshl_add_u64 v[218:219], s[38:39], 0, v[134:135]
	s_mov_b32 m0, s53
	s_nop 0
	global_load_lds_dwordx4 v[218:219], off
	s_waitcnt vmcnt(10)
	s_barrier
	s_waitcnt lgkmcnt(0)
	s_waitcnt lgkmcnt(0)
	v_mfma_f32_16x16x32_bf16 v[118:121], v[200:203], v[168:171], v[118:121]
	v_mfma_f32_16x16x32_bf16 v[110:113], v[208:211], v[168:171], v[110:113]
	v_mfma_f32_16x16x32_bf16 v[102:105], v[200:203], v[176:179], v[102:105]
	v_mfma_f32_16x16x32_bf16 v[94:97], v[208:211], v[176:179], v[94:97]
	v_mfma_f32_16x16x32_bf16 v[86:89], v[200:203], v[184:187], v[86:89]
	v_mfma_f32_16x16x32_bf16 v[78:81], v[208:211], v[184:187], v[78:81]
	v_mfma_f32_16x16x32_bf16 v[70:73], v[200:203], v[192:195], v[70:73]
	v_mfma_f32_16x16x32_bf16 v[66:69], v[208:211], v[192:195], v[66:69]
	v_mfma_f32_16x16x32_bf16 v[118:121], v[204:207], v[172:175], v[118:121]
	v_mfma_f32_16x16x32_bf16 v[110:113], v[212:215], v[172:175], v[110:113]
	v_mfma_f32_16x16x32_bf16 v[102:105], v[204:207], v[180:183], v[102:105]
	v_mfma_f32_16x16x32_bf16 v[94:97], v[212:215], v[180:183], v[94:97]
	v_mfma_f32_16x16x32_bf16 v[86:89], v[204:207], v[188:191], v[86:89]
	v_mfma_f32_16x16x32_bf16 v[78:81], v[212:215], v[188:191], v[78:81]
	v_mfma_f32_16x16x32_bf16 v[70:73], v[204:207], v[196:199], v[70:73]
	v_mfma_f32_16x16x32_bf16 v[66:69], v[212:215], v[196:199], v[66:69]
	s_mov_b32 m0, s6
	v_lshl_add_u64 v[220:221], s[40:41], 0, v[140:141]
	s_barrier
	ds_read_b128 v[168:171], v153 offset:16384
	ds_read_b128 v[172:175], v153 offset:17408
	ds_read_b128 v[176:179], v153 offset:18432
	ds_read_b128 v[180:183], v153 offset:19456
	ds_read_b128 v[184:187], v153 offset:20480
	ds_read_b128 v[188:191], v153 offset:21504
	ds_read_b128 v[192:195], v153 offset:22528
	ds_read_b128 v[196:199], v153 offset:23552
	global_load_lds_dwordx4 v[220:221], off
	v_lshl_add_u64 v[222:223], s[40:41], 0, v[136:137]
	s_mov_b32 m0, s7
	s_nop 0
	global_load_lds_dwordx4 v[222:223], off
	s_waitcnt vmcnt(10)
	s_barrier
	s_waitcnt lgkmcnt(0)
	s_waitcnt lgkmcnt(0)
	v_mfma_f32_16x16x32_bf16 v[62:65], v[146:149], v[168:171], v[62:65]
	v_mfma_f32_16x16x32_bf16 v[58:61], v[160:163], v[168:171], v[58:61]
	v_mfma_f32_16x16x32_bf16 v[50:53], v[146:149], v[176:179], v[50:53]
	v_mfma_f32_16x16x32_bf16 v[42:45], v[160:163], v[176:179], v[42:45]
	v_mfma_f32_16x16x32_bf16 v[34:37], v[146:149], v[184:187], v[34:37]
	v_mfma_f32_16x16x32_bf16 v[26:29], v[160:163], v[184:187], v[26:29]
	v_mfma_f32_16x16x32_bf16 v[18:21], v[146:149], v[192:195], v[18:21]
	v_mfma_f32_16x16x32_bf16 v[10:13], v[160:163], v[192:195], v[10:13]
	v_mfma_f32_16x16x32_bf16 v[62:65], v[156:159], v[172:175], v[62:65]
	v_mfma_f32_16x16x32_bf16 v[58:61], v[164:167], v[172:175], v[58:61]
	v_mfma_f32_16x16x32_bf16 v[50:53], v[156:159], v[180:183], v[50:53]
	v_mfma_f32_16x16x32_bf16 v[42:45], v[164:167], v[180:183], v[42:45]
	v_mfma_f32_16x16x32_bf16 v[34:37], v[156:159], v[188:191], v[34:37]
	v_mfma_f32_16x16x32_bf16 v[26:29], v[164:167], v[188:191], v[26:29]
	v_mfma_f32_16x16x32_bf16 v[18:21], v[156:159], v[196:199], v[18:21]
	v_mfma_f32_16x16x32_bf16 v[10:13], v[164:167], v[196:199], v[10:13]
	s_barrier
	s_add_u32 s0, s38, 0x40000
	s_addc_u32 s1, s39, 0
	s_mov_b32 m0, s54
	v_lshl_add_u64 v[146:147], s[0:1], 0, v[138:139]
	global_load_lds_dwordx4 v[146:147], off
	v_lshl_add_u64 v[146:147], s[0:1], 0, v[134:135]
	s_add_i32 m0, s54, 0x2000
	s_nop 0
	global_load_lds_dwordx4 v[146:147], off
	s_waitcnt vmcnt(10)
	s_barrier
	v_mfma_f32_16x16x32_bf16 v[54:57], v[200:203], v[168:171], v[54:57]
	v_mfma_f32_16x16x32_bf16 v[46:49], v[208:211], v[168:171], v[46:49]
	v_mfma_f32_16x16x32_bf16 v[38:41], v[200:203], v[176:179], v[38:41]
	v_mfma_f32_16x16x32_bf16 v[30:33], v[208:211], v[176:179], v[30:33]
	v_mfma_f32_16x16x32_bf16 v[22:25], v[200:203], v[184:187], v[22:25]
	v_mfma_f32_16x16x32_bf16 v[14:17], v[208:211], v[184:187], v[14:17]
	v_mfma_f32_16x16x32_bf16 v[6:9], v[200:203], v[192:195], v[6:9]
	v_mfma_f32_16x16x32_bf16 v[2:5], v[208:211], v[192:195], v[2:5]
	v_mfma_f32_16x16x32_bf16 v[54:57], v[204:207], v[172:175], v[54:57]
	v_mfma_f32_16x16x32_bf16 v[46:49], v[212:215], v[172:175], v[46:49]
	v_mfma_f32_16x16x32_bf16 v[38:41], v[204:207], v[180:183], v[38:41]
	v_mfma_f32_16x16x32_bf16 v[30:33], v[212:215], v[180:183], v[30:33]
	v_mfma_f32_16x16x32_bf16 v[22:25], v[204:207], v[188:191], v[22:25]
	v_mfma_f32_16x16x32_bf16 v[14:17], v[212:215], v[188:191], v[14:17]
	v_mfma_f32_16x16x32_bf16 v[6:9], v[204:207], v[196:199], v[6:9]
	v_mfma_f32_16x16x32_bf16 v[2:5], v[212:215], v[196:199], v[2:5]
	s_add_i32 s70, 0, 0x18000
	v_add_u32_e32 v155, s70, v151
	s_barrier
	ds_read_b128 v[146:149], v155
	ds_read_b128 v[156:159], v155 offset:1024
	ds_read_b128 v[160:163], v155 offset:2048
	ds_read_b128 v[164:167], v155 offset:3072
	s_add_u32 s0, s40, 0x40000
	s_addc_u32 s1, s41, 0
	s_mov_b32 m0, s29
	v_lshl_add_u64 v[200:201], s[0:1], 0, v[140:141]
	ds_read_b128 v[168:171], v153 offset:32768
	ds_read_b128 v[172:175], v153 offset:33792
	ds_read_b128 v[176:179], v153 offset:34816
	ds_read_b128 v[180:183], v153 offset:35840
	ds_read_b128 v[184:187], v153 offset:36864
	ds_read_b128 v[188:191], v153 offset:37888
	ds_read_b128 v[192:195], v153 offset:38912
	ds_read_b128 v[196:199], v153 offset:39936
	global_load_lds_dwordx4 v[200:201], off
	v_lshl_add_u64 v[200:201], s[0:1], 0, v[136:137]
	s_mov_b32 m0, s42
	s_nop 0
	global_load_lds_dwordx4 v[200:201], off
	s_waitcnt lgkmcnt(8)
	s_waitcnt vmcnt(10)
	s_barrier
	s_waitcnt lgkmcnt(0)
	s_waitcnt lgkmcnt(0)
	v_mfma_f32_16x16x32_bf16 v[126:129], v[146:149], v[168:171], v[126:129]
	v_mfma_f32_16x16x32_bf16 v[122:125], v[160:163], v[168:171], v[122:125]
	v_mfma_f32_16x16x32_bf16 v[114:117], v[146:149], v[176:179], v[114:117]
	v_mfma_f32_16x16x32_bf16 v[106:109], v[160:163], v[176:179], v[106:109]
	v_mfma_f32_16x16x32_bf16 v[98:101], v[146:149], v[184:187], v[98:101]
	v_mfma_f32_16x16x32_bf16 v[90:93], v[160:163], v[184:187], v[90:93]
	v_mfma_f32_16x16x32_bf16 v[82:85], v[146:149], v[192:195], v[82:85]
	v_mfma_f32_16x16x32_bf16 v[74:77], v[160:163], v[192:195], v[74:77]
	v_mfma_f32_16x16x32_bf16 v[126:129], v[156:159], v[172:175], v[126:129]
	v_mfma_f32_16x16x32_bf16 v[122:125], v[164:167], v[172:175], v[122:125]
	v_mfma_f32_16x16x32_bf16 v[114:117], v[156:159], v[180:183], v[114:117]
	v_mfma_f32_16x16x32_bf16 v[106:109], v[164:167], v[180:183], v[106:109]
	v_mfma_f32_16x16x32_bf16 v[98:101], v[156:159], v[188:191], v[98:101]
	v_mfma_f32_16x16x32_bf16 v[90:93], v[164:167], v[188:191], v[90:93]
	v_mfma_f32_16x16x32_bf16 v[82:85], v[156:159], v[196:199], v[82:85]
	v_mfma_f32_16x16x32_bf16 v[74:77], v[164:167], v[196:199], v[74:77]
	s_barrier
	s_add_i32 s40, 0, 0x1c000
	s_add_i32 s0, s70, s5
	v_add_u32_e32 v155, s40, v151
	v_lshl_add_u64 v[216:217], v[216:217], 0, s[26:27]
	s_mov_b32 m0, s0
	ds_read_b128 v[200:203], v155
	ds_read_b128 v[204:207], v155 offset:1024
	ds_read_b128 v[208:211], v155 offset:2048
	ds_read_b128 v[212:215], v155 offset:3072
	global_load_lds_dwordx4 v[216:217], off
	v_lshl_add_u64 v[216:217], v[218:219], 0, s[26:27]
	s_add_i32 m0, s0, 0x2000
	s_nop 0
	global_load_lds_dwordx4 v[216:217], off
	s_waitcnt vmcnt(10)
	s_barrier
	s_waitcnt lgkmcnt(0)
	s_waitcnt lgkmcnt(0)
	v_mfma_f32_16x16x32_bf16 v[118:121], v[200:203], v[168:171], v[118:121]
	v_mfma_f32_16x16x32_bf16 v[110:113], v[208:211], v[168:171], v[110:113]
	v_mfma_f32_16x16x32_bf16 v[102:105], v[200:203], v[176:179], v[102:105]
	v_mfma_f32_16x16x32_bf16 v[94:97], v[208:211], v[176:179], v[94:97]
	v_mfma_f32_16x16x32_bf16 v[86:89], v[200:203], v[184:187], v[86:89]
	v_mfma_f32_16x16x32_bf16 v[78:81], v[208:211], v[184:187], v[78:81]
	v_mfma_f32_16x16x32_bf16 v[70:73], v[200:203], v[192:195], v[70:73]
	v_mfma_f32_16x16x32_bf16 v[66:69], v[208:211], v[192:195], v[66:69]
	v_mfma_f32_16x16x32_bf16 v[118:121], v[204:207], v[172:175], v[118:121]
	v_mfma_f32_16x16x32_bf16 v[110:113], v[212:215], v[172:175], v[110:113]
	v_mfma_f32_16x16x32_bf16 v[102:105], v[204:207], v[180:183], v[102:105]
	v_mfma_f32_16x16x32_bf16 v[94:97], v[212:215], v[180:183], v[94:97]
	v_mfma_f32_16x16x32_bf16 v[86:89], v[204:207], v[188:191], v[86:89]
	v_mfma_f32_16x16x32_bf16 v[78:81], v[212:215], v[188:191], v[78:81]
	v_mfma_f32_16x16x32_bf16 v[70:73], v[204:207], v[196:199], v[70:73]
	v_mfma_f32_16x16x32_bf16 v[66:69], v[212:215], v[196:199], v[66:69]
	s_mov_b32 m0, s46
	v_lshl_add_u64 v[216:217], v[220:221], 0, s[26:27]
	s_barrier
	ds_read_b128 v[168:171], v153 offset:49152
	ds_read_b128 v[172:175], v153 offset:50176
	ds_read_b128 v[176:179], v153 offset:51200
	ds_read_b128 v[180:183], v153 offset:52224
	ds_read_b128 v[184:187], v153 offset:53248
	ds_read_b128 v[188:191], v153 offset:54272
	ds_read_b128 v[192:195], v153 offset:55296
	ds_read_b128 v[196:199], v153 offset:56320
	global_load_lds_dwordx4 v[216:217], off
	v_lshl_add_u64 v[216:217], v[222:223], 0, s[26:27]
	s_mov_b32 m0, s47
	s_nop 0
	global_load_lds_dwordx4 v[216:217], off
	s_waitcnt vmcnt(10)
	s_barrier
	s_waitcnt lgkmcnt(0)
	s_waitcnt lgkmcnt(0)
	v_mfma_f32_16x16x32_bf16 v[62:65], v[146:149], v[168:171], v[62:65]
	v_mfma_f32_16x16x32_bf16 v[58:61], v[160:163], v[168:171], v[58:61]
	v_mfma_f32_16x16x32_bf16 v[50:53], v[146:149], v[176:179], v[50:53]
	v_mfma_f32_16x16x32_bf16 v[42:45], v[160:163], v[176:179], v[42:45]
	v_mfma_f32_16x16x32_bf16 v[34:37], v[146:149], v[184:187], v[34:37]
	v_mfma_f32_16x16x32_bf16 v[26:29], v[160:163], v[184:187], v[26:29]
	v_mfma_f32_16x16x32_bf16 v[18:21], v[146:149], v[192:195], v[18:21]
	v_mfma_f32_16x16x32_bf16 v[10:13], v[160:163], v[192:195], v[10:13]
	v_mfma_f32_16x16x32_bf16 v[62:65], v[156:159], v[172:175], v[62:65]
	v_mfma_f32_16x16x32_bf16 v[58:61], v[164:167], v[172:175], v[58:61]
	v_mfma_f32_16x16x32_bf16 v[50:53], v[156:159], v[180:183], v[50:53]
	v_mfma_f32_16x16x32_bf16 v[42:45], v[164:167], v[180:183], v[42:45]
	v_mfma_f32_16x16x32_bf16 v[34:37], v[156:159], v[188:191], v[34:37]
	v_mfma_f32_16x16x32_bf16 v[26:29], v[164:167], v[188:191], v[26:29]
	v_mfma_f32_16x16x32_bf16 v[18:21], v[156:159], v[196:199], v[18:21]
	v_mfma_f32_16x16x32_bf16 v[10:13], v[164:167], v[196:199], v[10:13]
	s_barrier
	s_add_u32 s0, s38, 0x40080
	s_addc_u32 s1, s39, 0
	s_add_i32 s38, s40, s5
	v_lshl_add_u64 v[146:147], s[0:1], 0, v[138:139]
	s_mov_b32 m0, s38
	s_nop 0
	global_load_lds_dwordx4 v[146:147], off
	v_lshl_add_u64 v[146:147], s[0:1], 0, v[134:135]
	s_add_i32 m0, s38, 0x2000
	s_nop 0
	global_load_lds_dwordx4 v[146:147], off
	s_waitcnt vmcnt(10)
	s_barrier
	v_mfma_f32_16x16x32_bf16 v[54:57], v[200:203], v[168:171], v[54:57]
	v_mfma_f32_16x16x32_bf16 v[46:49], v[208:211], v[168:171], v[46:49]
	v_mfma_f32_16x16x32_bf16 v[38:41], v[200:203], v[176:179], v[38:41]
	v_mfma_f32_16x16x32_bf16 v[30:33], v[208:211], v[176:179], v[30:33]
	v_mfma_f32_16x16x32_bf16 v[22:25], v[200:203], v[184:187], v[22:25]
	v_mfma_f32_16x16x32_bf16 v[14:17], v[208:211], v[184:187], v[14:17]
	v_mfma_f32_16x16x32_bf16 v[6:9], v[200:203], v[192:195], v[6:9]
	v_mfma_f32_16x16x32_bf16 v[2:5], v[208:211], v[192:195], v[2:5]
	v_mfma_f32_16x16x32_bf16 v[54:57], v[204:207], v[172:175], v[54:57]
	v_mfma_f32_16x16x32_bf16 v[46:49], v[212:215], v[172:175], v[46:49]
	v_mfma_f32_16x16x32_bf16 v[38:41], v[204:207], v[180:183], v[38:41]
	v_mfma_f32_16x16x32_bf16 v[30:33], v[212:215], v[180:183], v[30:33]
	v_mfma_f32_16x16x32_bf16 v[22:25], v[204:207], v[188:191], v[22:25]
	v_mfma_f32_16x16x32_bf16 v[14:17], v[212:215], v[188:191], v[14:17]
	v_mfma_f32_16x16x32_bf16 v[6:9], v[204:207], v[196:199], v[6:9]
	v_mfma_f32_16x16x32_bf16 v[2:5], v[212:215], v[196:199], v[2:5]
	s_add_i32 s69, s69, 2
	s_add_u32 s66, s66, 0x100
	s_addc_u32 s67, s67, 0
	s_add_u32 s36, s36, 0x100
	s_addc_u32 s37, s37, 0
	s_cmp_gt_u32 s69, 13
	s_barrier
	s_cbranch_scc0 .LBB0_434
	v_mov_b32_e32 v147, v131
	v_mov_b32_e32 v146, v133
	s_lshl_b32 s0, s58, 8
	s_or_b32 s0, s0, s45
	v_lshl_add_u32 v146, v146, 3, s0
	s_lshl_b32 s0, s59, 8
	s_add_i32 s0, s0, s44
	v_add_u32_e32 v155, s0, v147
	v_mov_b32_e32 v148, v155
	v_ashrrev_i32_e32 v147, 31, v146
	v_ashrrev_i32_e32 v149, 31, v148
	v_lshlrev_b64 v[148:149], 10, v[148:149]
	v_lshl_add_u64 v[148:149], v[148:149], 0, v[146:147]
	v_lshlrev_b64 v[148:149], 1, v[148:149]
	v_lshl_add_u64 v[176:177], s[10:11], 0, v[148:149]
	global_load_dwordx4 v[156:159], v[176:177], off
	global_load_dwordx4 v[160:163], v[176:177], off offset:256
	v_add_co_u32_e32 v168, vcc, s49, v176
	v_lshl_add_u64 v[148:149], s[12:13], 0, v[148:149]
	s_nop 0
	v_addc_co_u32_e32 v169, vcc, 0, v177, vcc
	global_load_dwordx4 v[164:167], v[168:169], off
	s_nop 0
	global_load_dwordx4 v[168:171], v[168:169], off offset:256
	v_add_co_u32_e32 v178, vcc, s43, v176
	s_mov_b32 s58, s57
	s_nop 0
	v_addc_co_u32_e32 v179, vcc, 0, v177, vcc
	global_load_dwordx4 v[172:175], v[178:179], off
	v_add_co_u32_e32 v184, vcc, s48, v176
	s_mov_b32 s59, s56
	s_nop 0
	v_addc_co_u32_e32 v185, vcc, 0, v177, vcc
	global_load_dwordx4 v[176:179], v[178:179], off offset:256
	s_nop 0
	global_load_dwordx4 v[180:183], v[184:185], off
	s_nop 0
	global_load_dwordx4 v[184:187], v[184:185], off offset:256
	v_add_co_u32_e32 v188, vcc, s49, v148
	s_waitcnt vmcnt(0) lgkmcnt(0)
	v_lshlrev_b32_e32 v190, 16, v156
	v_and_b32_e32 v191, 0xffff0000, v156
	v_lshlrev_b32_e32 v156, 16, v157
	v_and_b32_e32 v157, 0xffff0000, v157
	v_lshlrev_b32_e32 v192, 16, v158
	v_and_b32_e32 v193, 0xffff0000, v158
	v_lshlrev_b32_e32 v194, 16, v160
	v_and_b32_e32 v195, 0xffff0000, v160
	v_lshlrev_b32_e32 v160, 16, v161
	v_and_b32_e32 v161, 0xffff0000, v161
	v_lshlrev_b32_e32 v196, 16, v162
	v_and_b32_e32 v197, 0xffff0000, v162
	v_lshlrev_b32_e32 v162, 16, v163
	v_and_b32_e32 v163, 0xffff0000, v163
	v_lshlrev_b32_e32 v158, 16, v159
	v_and_b32_e32 v159, 0xffff0000, v159
	v_pk_fma_f32 v[128:129], v[156:157], s[28:29], v[128:129] op_sel_hi:[1,0,1]
	v_pk_fma_f32 v[122:123], v[192:193], s[28:29], v[122:123] op_sel_hi:[1,0,1]
	v_pk_fma_f32 v[120:121], v[160:161], s[28:29], v[120:121] op_sel_hi:[1,0,1]
	v_pk_fma_f32 v[156:157], v[162:163], s[28:29], v[112:113] op_sel_hi:[1,0,1]
	v_lshlrev_b32_e32 v160, 16, v164
	v_and_b32_e32 v161, 0xffff0000, v164
	v_lshlrev_b32_e32 v162, 16, v165
	v_and_b32_e32 v163, 0xffff0000, v165
	v_lshlrev_b32_e32 v164, 16, v166
	v_and_b32_e32 v165, 0xffff0000, v166
	v_lshlrev_b32_e32 v166, 16, v167
	v_and_b32_e32 v167, 0xffff0000, v167
	v_pk_fma_f32 v[126:127], v[190:191], s[28:29], v[126:127] op_sel_hi:[1,0,1]
	v_pk_fma_f32 v[124:125], v[158:159], s[28:29], v[124:125] op_sel_hi:[1,0,1]
	v_cvt_pk_bf16_f32 v112, v122, v123
	v_pk_fma_f32 v[116:117], v[162:163], s[28:29], v[116:117] op_sel_hi:[1,0,1]
	v_pk_fma_f32 v[114:115], v[160:161], s[28:29], v[114:115] op_sel_hi:[1,0,1]
	v_pk_fma_f32 v[122:123], v[166:167], s[28:29], v[108:109] op_sel_hi:[1,0,1]
	v_pk_fma_f32 v[108:109], v[164:165], s[28:29], v[106:107] op_sel_hi:[1,0,1]
	v_addc_co_u32_e32 v189, vcc, 0, v149, vcc
	v_pk_fma_f32 v[118:119], v[194:195], s[28:29], v[118:119] op_sel_hi:[1,0,1]
	v_pk_fma_f32 v[158:159], v[196:197], s[28:29], v[110:111] op_sel_hi:[1,0,1]
	v_cvt_pk_bf16_f32 v110, v126, v127
	v_cvt_pk_bf16_f32 v111, v128, v129
	v_cvt_pk_bf16_f32 v113, v124, v125
	v_cvt_pk_bf16_f32 v106, v114, v115
	v_cvt_pk_bf16_f32 v107, v116, v117
	v_cvt_pk_bf16_f32 v108, v108, v109
	v_cvt_pk_bf16_f32 v109, v122, v123
	v_lshlrev_b32_e32 v190, 16, v168
	v_cvt_pk_bf16_f32 v118, v118, v119
	v_cvt_pk_bf16_f32 v119, v120, v121
	v_cvt_pk_bf16_f32 v120, v158, v159
	v_cvt_pk_bf16_f32 v121, v156, v157
	global_store_dwordx4 v[148:149], v[110:113], off
	global_store_dwordx4 v[148:149], v[118:121], off offset:256
	global_store_dwordx4 v[188:189], v[106:109], off
	v_and_b32_e32 v191, 0xffff0000, v168
	v_lshlrev_b32_e32 v110, 16, v171
	v_lshlrev_b32_e32 v106, 16, v169
	v_and_b32_e32 v107, 0xffff0000, v169
	v_lshlrev_b32_e32 v108, 16, v170
	v_and_b32_e32 v109, 0xffff0000, v170
	v_and_b32_e32 v111, 0xffff0000, v171
	v_pk_fma_f32 v[104:105], v[106:107], s[28:29], v[104:105] op_sel_hi:[1,0,1]
	v_pk_fma_f32 v[102:103], v[190:191], s[28:29], v[102:103] op_sel_hi:[1,0,1]
	v_pk_fma_f32 v[106:107], v[110:111], s[28:29], v[96:97] op_sel_hi:[1,0,1]
	v_pk_fma_f32 v[96:97], v[108:109], s[28:29], v[94:95] op_sel_hi:[1,0,1]
	v_cvt_pk_bf16_f32 v94, v102, v103
	v_cvt_pk_bf16_f32 v95, v104, v105
	v_cvt_pk_bf16_f32 v96, v96, v97
	v_cvt_pk_bf16_f32 v97, v106, v107
	global_store_dwordx4 v[188:189], v[94:97], off offset:256
	v_lshlrev_b32_e32 v102, 16, v174
	v_and_b32_e32 v103, 0xffff0000, v174
	v_lshlrev_b32_e32 v94, 16, v172
	v_and_b32_e32 v95, 0xffff0000, v172
	v_lshlrev_b32_e32 v96, 16, v173
	v_and_b32_e32 v97, 0xffff0000, v173
	v_lshlrev_b32_e32 v104, 16, v175
	v_and_b32_e32 v105, 0xffff0000, v175
	v_pk_fma_f32 v[94:95], v[94:95], s[28:29], v[98:99] op_sel_hi:[1,0,1]
	v_pk_fma_f32 v[96:97], v[96:97], s[28:29], v[100:101] op_sel_hi:[1,0,1]
	v_pk_fma_f32 v[98:99], v[104:105], s[28:29], v[92:93] op_sel_hi:[1,0,1]
	v_pk_fma_f32 v[92:93], v[102:103], s[28:29], v[90:91] op_sel_hi:[1,0,1]
	v_cvt_pk_bf16_f32 v90, v94, v95
	v_add_co_u32_e32 v94, vcc, s43, v148
	v_cvt_pk_bf16_f32 v91, v96, v97
	v_cvt_pk_bf16_f32 v92, v92, v93
	v_cvt_pk_bf16_f32 v93, v98, v99
	v_addc_co_u32_e32 v95, vcc, 0, v149, vcc
	global_store_dwordx4 v[94:95], v[90:93], off
	v_lshlrev_b32_e32 v96, 16, v178
	v_and_b32_e32 v97, 0xffff0000, v178
	v_lshlrev_b32_e32 v90, 16, v176
	v_and_b32_e32 v91, 0xffff0000, v176
	v_lshlrev_b32_e32 v92, 16, v177
	v_and_b32_e32 v93, 0xffff0000, v177
	v_lshlrev_b32_e32 v98, 16, v179
	v_and_b32_e32 v99, 0xffff0000, v179
	v_pk_fma_f32 v[88:89], v[92:93], s[28:29], v[88:89] op_sel_hi:[1,0,1]
	v_pk_fma_f32 v[86:87], v[90:91], s[28:29], v[86:87] op_sel_hi:[1,0,1]
	v_pk_fma_f32 v[90:91], v[98:99], s[28:29], v[80:81] op_sel_hi:[1,0,1]
	v_pk_fma_f32 v[80:81], v[96:97], s[28:29], v[78:79] op_sel_hi:[1,0,1]
	v_cvt_pk_bf16_f32 v78, v86, v87
	v_cvt_pk_bf16_f32 v79, v88, v89
	v_cvt_pk_bf16_f32 v80, v80, v81
	v_cvt_pk_bf16_f32 v81, v90, v91
	global_store_dwordx4 v[94:95], v[78:81], off offset:256
	v_lshlrev_b32_e32 v86, 16, v182
	v_and_b32_e32 v87, 0xffff0000, v182
	v_lshlrev_b32_e32 v78, 16, v180
	v_and_b32_e32 v79, 0xffff0000, v180
	v_lshlrev_b32_e32 v80, 16, v181
	v_and_b32_e32 v81, 0xffff0000, v181
	v_lshlrev_b32_e32 v88, 16, v183
	v_and_b32_e32 v89, 0xffff0000, v183
	v_pk_fma_f32 v[78:79], v[78:79], s[28:29], v[82:83] op_sel_hi:[1,0,1]
	v_pk_fma_f32 v[80:81], v[80:81], s[28:29], v[84:85] op_sel_hi:[1,0,1]
	v_pk_fma_f32 v[82:83], v[88:89], s[28:29], v[76:77] op_sel_hi:[1,0,1]
	v_pk_fma_f32 v[76:77], v[86:87], s[28:29], v[74:75] op_sel_hi:[1,0,1]
	v_cvt_pk_bf16_f32 v74, v78, v79
	v_add_co_u32_e32 v78, vcc, s48, v148
	v_cvt_pk_bf16_f32 v75, v80, v81
	v_cvt_pk_bf16_f32 v76, v76, v77
	v_cvt_pk_bf16_f32 v77, v82, v83
	v_addc_co_u32_e32 v79, vcc, 0, v149, vcc
	global_store_dwordx4 v[78:79], v[74:77], off
	v_lshlrev_b32_e32 v80, 16, v186
	v_and_b32_e32 v81, 0xffff0000, v186
	v_lshlrev_b32_e32 v74, 16, v184
	v_and_b32_e32 v75, 0xffff0000, v184
	v_lshlrev_b32_e32 v76, 16, v185
	v_and_b32_e32 v77, 0xffff0000, v185
	v_lshlrev_b32_e32 v82, 16, v187
	v_and_b32_e32 v83, 0xffff0000, v187
	v_pk_fma_f32 v[72:73], v[76:77], s[28:29], v[72:73] op_sel_hi:[1,0,1]
	v_pk_fma_f32 v[70:71], v[74:75], s[28:29], v[70:71] op_sel_hi:[1,0,1]
	v_pk_fma_f32 v[74:75], v[82:83], s[28:29], v[68:69] op_sel_hi:[1,0,1]
	v_pk_fma_f32 v[68:69], v[80:81], s[28:29], v[66:67] op_sel_hi:[1,0,1]
	v_cvt_pk_bf16_f32 v66, v70, v71
	v_cvt_pk_bf16_f32 v67, v72, v73
	v_cvt_pk_bf16_f32 v68, v68, v69
	v_cvt_pk_bf16_f32 v69, v74, v75
	global_store_dwordx4 v[78:79], v[66:69], off offset:256
	s_nop 1
	v_add_u32_e32 v66, 0x80, v155
	s_nop 0
	v_ashrrev_i32_e32 v67, 31, v66
	v_lshlrev_b64 v[66:67], 10, v[66:67]
	v_lshl_add_u64 v[66:67], v[66:67], 0, v[146:147]
	v_lshlrev_b64 v[98:99], 1, v[66:67]
	v_lshl_add_u64 v[90:91], s[10:11], 0, v[98:99]
	global_load_dwordx4 v[66:69], v[90:91], off
	global_load_dwordx4 v[70:73], v[90:91], off offset:256
	v_add_co_u32_e32 v78, vcc, s49, v90
	s_waitcnt vmcnt(0) lgkmcnt(0)
	v_lshlrev_b32_e32 v100, 16, v66
	v_addc_co_u32_e32 v79, vcc, 0, v91, vcc
	global_load_dwordx4 v[74:77], v[78:79], off
	s_nop 0
	global_load_dwordx4 v[78:81], v[78:79], off offset:256
	v_add_co_u32_e32 v86, vcc, s43, v90
	v_and_b32_e32 v101, 0xffff0000, v66
	s_nop 0
	v_addc_co_u32_e32 v87, vcc, 0, v91, vcc
	global_load_dwordx4 v[82:85], v[86:87], off
	s_nop 0
	global_load_dwordx4 v[86:89], v[86:87], off offset:256
	v_add_co_u32_e32 v94, vcc, s48, v90
	v_lshlrev_b32_e32 v66, 16, v67
	s_nop 0
	v_addc_co_u32_e32 v95, vcc, 0, v91, vcc
	global_load_dwordx4 v[90:93], v[94:95], off
	s_nop 0
	global_load_dwordx4 v[94:97], v[94:95], off offset:256
	v_and_b32_e32 v67, 0xffff0000, v67
	v_lshlrev_b32_e32 v102, 16, v68
	v_and_b32_e32 v103, 0xffff0000, v68
	v_lshlrev_b32_e32 v68, 16, v69
	v_and_b32_e32 v69, 0xffff0000, v69
	v_pk_fma_f32 v[64:65], v[66:67], s[28:29], v[64:65] op_sel_hi:[1,0,1]
	v_pk_fma_f32 v[62:63], v[100:101], s[28:29], v[62:63] op_sel_hi:[1,0,1]
	v_pk_fma_f32 v[66:67], v[68:69], s[28:29], v[60:61] op_sel_hi:[1,0,1]
	v_pk_fma_f32 v[60:61], v[102:103], s[28:29], v[58:59] op_sel_hi:[1,0,1]
	v_cvt_pk_bf16_f32 v58, v62, v63
	v_cvt_pk_bf16_f32 v59, v64, v65
	v_cvt_pk_bf16_f32 v60, v60, v61
	v_cvt_pk_bf16_f32 v61, v66, v67
	v_lshl_add_u64 v[62:63], s[12:13], 0, v[98:99]
	global_store_dwordx4 v[62:63], v[58:61], off
	v_lshlrev_b32_e32 v64, 16, v72
	v_and_b32_e32 v65, 0xffff0000, v72
	v_lshlrev_b32_e32 v58, 16, v70
	v_and_b32_e32 v59, 0xffff0000, v70
	v_lshlrev_b32_e32 v60, 16, v71
	v_and_b32_e32 v61, 0xffff0000, v71
	v_lshlrev_b32_e32 v66, 16, v73
	v_and_b32_e32 v67, 0xffff0000, v73
	v_pk_fma_f32 v[56:57], v[60:61], s[28:29], v[56:57] op_sel_hi:[1,0,1]
	v_pk_fma_f32 v[54:55], v[58:59], s[28:29], v[54:55] op_sel_hi:[1,0,1]
	v_pk_fma_f32 v[58:59], v[66:67], s[28:29], v[48:49] op_sel_hi:[1,0,1]
	v_pk_fma_f32 v[48:49], v[64:65], s[28:29], v[46:47] op_sel_hi:[1,0,1]
	v_cvt_pk_bf16_f32 v46, v54, v55
	v_cvt_pk_bf16_f32 v47, v56, v57
	v_cvt_pk_bf16_f32 v48, v48, v49
	v_cvt_pk_bf16_f32 v49, v58, v59
	global_store_dwordx4 v[62:63], v[46:49], off offset:256
	s_waitcnt vmcnt(0) lgkmcnt(0)
	v_lshlrev_b32_e32 v54, 16, v76
	v_lshlrev_b32_e32 v46, 16, v74
	v_and_b32_e32 v47, 0xffff0000, v74
	v_lshlrev_b32_e32 v48, 16, v75
	v_and_b32_e32 v49, 0xffff0000, v75
	v_and_b32_e32 v55, 0xffff0000, v76
	v_lshlrev_b32_e32 v56, 16, v77
	v_and_b32_e32 v57, 0xffff0000, v77
	v_pk_fma_f32 v[46:47], v[46:47], s[28:29], v[50:51] op_sel_hi:[1,0,1]
	v_pk_fma_f32 v[48:49], v[48:49], s[28:29], v[52:53] op_sel_hi:[1,0,1]
	v_pk_fma_f32 v[50:51], v[56:57], s[28:29], v[44:45] op_sel_hi:[1,0,1]
	v_pk_fma_f32 v[44:45], v[54:55], s[28:29], v[42:43] op_sel_hi:[1,0,1]
	v_cvt_pk_bf16_f32 v42, v46, v47
	v_add_co_u32_e32 v46, vcc, s49, v62
	v_cvt_pk_bf16_f32 v43, v48, v49
	v_cvt_pk_bf16_f32 v44, v44, v45
	v_cvt_pk_bf16_f32 v45, v50, v51
	v_addc_co_u32_e32 v47, vcc, 0, v63, vcc
	global_store_dwordx4 v[46:47], v[42:45], off
	v_lshlrev_b32_e32 v48, 16, v80
	v_and_b32_e32 v49, 0xffff0000, v80
	v_lshlrev_b32_e32 v42, 16, v78
	v_and_b32_e32 v43, 0xffff0000, v78
	v_lshlrev_b32_e32 v44, 16, v79
	v_and_b32_e32 v45, 0xffff0000, v79
	v_lshlrev_b32_e32 v50, 16, v81
	v_and_b32_e32 v51, 0xffff0000, v81
	v_pk_fma_f32 v[40:41], v[44:45], s[28:29], v[40:41] op_sel_hi:[1,0,1]
	v_pk_fma_f32 v[38:39], v[42:43], s[28:29], v[38:39] op_sel_hi:[1,0,1]
	v_pk_fma_f32 v[42:43], v[50:51], s[28:29], v[32:33] op_sel_hi:[1,0,1]
	v_pk_fma_f32 v[32:33], v[48:49], s[28:29], v[30:31] op_sel_hi:[1,0,1]
	v_cvt_pk_bf16_f32 v30, v38, v39
	v_cvt_pk_bf16_f32 v31, v40, v41
	v_cvt_pk_bf16_f32 v32, v32, v33
	v_cvt_pk_bf16_f32 v33, v42, v43
	global_store_dwordx4 v[46:47], v[30:33], off offset:256
	v_lshlrev_b32_e32 v38, 16, v84
	v_and_b32_e32 v39, 0xffff0000, v84
	v_lshlrev_b32_e32 v30, 16, v82
	v_and_b32_e32 v31, 0xffff0000, v82
	v_lshlrev_b32_e32 v32, 16, v83
	v_and_b32_e32 v33, 0xffff0000, v83
	v_lshlrev_b32_e32 v40, 16, v85
	v_and_b32_e32 v41, 0xffff0000, v85
	v_pk_fma_f32 v[30:31], v[30:31], s[28:29], v[34:35] op_sel_hi:[1,0,1]
	v_pk_fma_f32 v[32:33], v[32:33], s[28:29], v[36:37] op_sel_hi:[1,0,1]
	v_pk_fma_f32 v[34:35], v[40:41], s[28:29], v[28:29] op_sel_hi:[1,0,1]
	v_pk_fma_f32 v[28:29], v[38:39], s[28:29], v[26:27] op_sel_hi:[1,0,1]
	v_cvt_pk_bf16_f32 v26, v30, v31
	v_add_co_u32_e32 v30, vcc, s43, v62
	v_cvt_pk_bf16_f32 v27, v32, v33
	v_cvt_pk_bf16_f32 v28, v28, v29
	v_cvt_pk_bf16_f32 v29, v34, v35
	v_addc_co_u32_e32 v31, vcc, 0, v63, vcc
	global_store_dwordx4 v[30:31], v[26:29], off
	v_lshlrev_b32_e32 v32, 16, v88
	v_and_b32_e32 v33, 0xffff0000, v88
	v_lshlrev_b32_e32 v26, 16, v86
	v_and_b32_e32 v27, 0xffff0000, v86
	v_lshlrev_b32_e32 v28, 16, v87
	v_and_b32_e32 v29, 0xffff0000, v87
	v_lshlrev_b32_e32 v34, 16, v89
	v_and_b32_e32 v35, 0xffff0000, v89
	v_pk_fma_f32 v[24:25], v[28:29], s[28:29], v[24:25] op_sel_hi:[1,0,1]
	v_pk_fma_f32 v[22:23], v[26:27], s[28:29], v[22:23] op_sel_hi:[1,0,1]
	v_pk_fma_f32 v[26:27], v[34:35], s[28:29], v[16:17] op_sel_hi:[1,0,1]
	v_pk_fma_f32 v[16:17], v[32:33], s[28:29], v[14:15] op_sel_hi:[1,0,1]
	v_cvt_pk_bf16_f32 v14, v22, v23
	v_cvt_pk_bf16_f32 v15, v24, v25
	v_cvt_pk_bf16_f32 v16, v16, v17
	v_cvt_pk_bf16_f32 v17, v26, v27
	global_store_dwordx4 v[30:31], v[14:17], off offset:256
	v_lshlrev_b32_e32 v22, 16, v92
	v_and_b32_e32 v23, 0xffff0000, v92
	v_lshlrev_b32_e32 v14, 16, v90
	v_and_b32_e32 v15, 0xffff0000, v90
	v_lshlrev_b32_e32 v16, 16, v91
	v_and_b32_e32 v17, 0xffff0000, v91
	v_lshlrev_b32_e32 v24, 16, v93
	v_and_b32_e32 v25, 0xffff0000, v93
	v_pk_fma_f32 v[14:15], v[14:15], s[28:29], v[18:19] op_sel_hi:[1,0,1]
	v_pk_fma_f32 v[16:17], v[16:17], s[28:29], v[20:21] op_sel_hi:[1,0,1]
	v_pk_fma_f32 v[18:19], v[24:25], s[28:29], v[12:13] op_sel_hi:[1,0,1]
	v_pk_fma_f32 v[12:13], v[22:23], s[28:29], v[10:11] op_sel_hi:[1,0,1]
	v_cvt_pk_bf16_f32 v10, v14, v15
	v_add_co_u32_e32 v14, vcc, s48, v62
	v_cvt_pk_bf16_f32 v11, v16, v17
	v_cvt_pk_bf16_f32 v12, v12, v13
	v_cvt_pk_bf16_f32 v13, v18, v19
	v_addc_co_u32_e32 v15, vcc, 0, v63, vcc
	global_store_dwordx4 v[14:15], v[10:13], off
	v_lshlrev_b32_e32 v16, 16, v96
	v_and_b32_e32 v17, 0xffff0000, v96
	v_lshlrev_b32_e32 v10, 16, v94
	v_and_b32_e32 v11, 0xffff0000, v94
	v_lshlrev_b32_e32 v12, 16, v95
	v_and_b32_e32 v13, 0xffff0000, v95
	v_lshlrev_b32_e32 v18, 16, v97
	v_and_b32_e32 v19, 0xffff0000, v97
	v_pk_fma_f32 v[8:9], v[12:13], s[28:29], v[8:9] op_sel_hi:[1,0,1]
	v_pk_fma_f32 v[6:7], v[10:11], s[28:29], v[6:7] op_sel_hi:[1,0,1]
	v_pk_fma_f32 v[10:11], v[18:19], s[28:29], v[4:5] op_sel_hi:[1,0,1]
	v_pk_fma_f32 v[4:5], v[16:17], s[28:29], v[2:3] op_sel_hi:[1,0,1]
	v_cvt_pk_bf16_f32 v2, v6, v7
	v_cvt_pk_bf16_f32 v3, v8, v9
	v_cvt_pk_bf16_f32 v4, v4, v5
	v_cvt_pk_bf16_f32 v5, v10, v11
	s_and_b64 vcc, exec, s[30:31]
	global_store_dwordx4 v[14:15], v[2:5], off offset:256
	s_cbranch_vccz .LBB0_433
	s_waitcnt vmcnt(0)
	s_cmpk_gt_u32 s4, 0xff
	s_cbranch_scc1 .LBB0_438
	s_barrier

.LBB0_455:
	s_or_b64 exec, exec, s[18:19]
	s_lshl_b32 s0, s39, 8
	s_add_i32 s0, s0, s97
	s_ashr_i32 s1, s0, 31
	s_lshl_b64 s[18:19], s[0:1], 11
	v_lshl_add_u64 v[38:39], v[54:55], 0, s[18:19]
	v_add_co_u32_e32 v44, vcc, 0x4000, v38
	s_waitcnt lgkmcnt(0)
	s_barrier
	global_load_dwordx4 v[2:5], v[50:51], off
	global_load_dwordx4 v[6:9], v[50:51], off offset:1024
	global_load_dwordx4 v[10:13], v[52:53], off
	global_load_dwordx4 v[14:17], v[52:53], off offset:1024
	global_load_dwordx4 v[18:21], v[50:51], off offset:2048
	global_load_dwordx4 v[22:25], v[50:51], off offset:3072
	global_load_dwordx4 v[26:29], v[52:53], off offset:2048
	global_load_dwordx4 v[30:33], v[52:53], off offset:3072
	v_lshl_add_u64 v[42:43], v[38:39], 0, s[28:29]
	v_addc_co_u32_e32 v45, vcc, 0, v39, vcc
	global_load_dwordx2 v[36:37], v[38:39], off
	global_load_dwordx2 v[34:35], v[38:39], off offset:512
	global_load_dwordx2 v[40:41], v[38:39], off offset:1024
	s_nop 0
	global_load_dwordx2 v[38:39], v[38:39], off offset:1536
	s_nop 0
	global_load_dwordx2 v[60:61], v[44:45], off
	global_load_dwordx2 v[62:63], v[42:43], off offset:512
	global_load_dwordx2 v[64:65], v[42:43], off offset:1024
	global_load_dwordx2 v[66:67], v[42:43], off offset:1536
	s_mov_b32 s34, 0
	s_add_i32 s35, s0, 16
	s_mov_b32 s36, 0
	s_branch .LBB0_458

.LBB0_458:
	s_waitcnt vmcnt(0) lgkmcnt(0)
	v_lshlrev_b32_e32 v85, 16, v37
	v_lshlrev_b32_e32 v84, 16, v36
	v_and_b32_e32 v37, 0xffff0000, v37
	v_and_b32_e32 v36, 0xffff0000, v36
	v_pk_add_f32 v[68:69], v[84:85], v[36:37]
	v_lshlrev_b32_e32 v87, 16, v35
	v_lshlrev_b32_e32 v86, 16, v34
	v_and_b32_e32 v35, 0xffff0000, v35
	v_and_b32_e32 v34, 0xffff0000, v34
	v_lshlrev_b32_e32 v46, 16, v39
	v_and_b32_e32 v48, 0xffff0000, v39
	v_add_f32_e32 v39, v68, v69
	v_pk_add_f32 v[68:69], v[86:87], v[34:35]
	v_lshlrev_b32_e32 v42, 16, v40
	v_and_b32_e32 v43, 0xffff0000, v40
	v_lshlrev_b32_e32 v40, 16, v41
	v_and_b32_e32 v41, 0xffff0000, v41
	v_pk_add_f32 v[68:69], v[68:69], v[68:69] op_sel_hi:[0,1]
	v_lshlrev_b32_e32 v44, 16, v38
	v_and_b32_e32 v38, 0xffff0000, v38
	v_add_f32_e32 v49, 0, v39
	v_add_f32_e32 v45, v42, v43
	v_add_f32_e32 v39, v40, v41
	v_mov_b32_e32 v47, v69
	v_pk_add_f32 v[70:71], v[44:45], v[38:39]
	v_pk_add_f32 v[68:69], v[46:47], v[48:49]
	s_min_u32 s0, s36, 29
	v_pk_add_f32 v[68:69], v[70:71], v[68:69]
	s_lshl_b32 s0, s0, 3
	v_add_f32_e32 v39, v68, v69
	s_add_i32 s18, s35, s0
	s_nop 0
	v_add_f32_dpp v39, v39, v39 quad_perm:[1,0,3,2] row_mask:0xf bank_mask:0xf bound_ctrl:1
	s_nop 1
	v_add_f32_dpp v39, v39, v39 quad_perm:[2,3,0,1] row_mask:0xf bank_mask:0xf bound_ctrl:1
	s_nop 1
	v_add_f32_dpp v39, v39, v39 row_half_mirror row_mask:0xf bank_mask:0xf bound_ctrl:1
	s_nop 1
	v_add_f32_dpp v39, v39, v39 row_mirror row_mask:0xf bank_mask:0xf bound_ctrl:1
	s_nop 0
	v_readlane_b32 s19, v39, 16
	v_readlane_b32 s20, v39, 48
	v_readlane_b32 s0, v39, 0
	v_readlane_b32 s1, v39, 32
	v_mov_b32_e32 v68, s19
	v_mov_b32_e32 v69, s20
	v_pk_add_f32 v[68:69], s[0:1], v[68:69]
	s_nop 0
	v_add_f32_e32 v39, v68, v69
	v_fmac_f32_e32 v36, 0xba800000, v39
	v_fmac_f32_e32 v37, 0xba800000, v39
	v_fmac_f32_e32 v85, 0xba800000, v39
	v_fmac_f32_e32 v84, 0xba800000, v39
	v_mov_b32_e32 v88, v85
	v_mov_b32_e32 v89, v37
	v_mov_b32_e32 v85, v36
	v_fmac_f32_e32 v34, 0xba800000, v39
	v_fmac_f32_e32 v35, 0xba800000, v39
	v_fmac_f32_e32 v87, 0xba800000, v39
	v_pk_mul_f32 v[68:69], v[88:89], v[88:89]
	v_pk_mul_f32 v[36:37], v[84:85], v[84:85]
	v_fmac_f32_e32 v86, 0xba800000, v39
	v_mov_b32_e32 v90, v87
	v_mov_b32_e32 v91, v35
	v_mov_b32_e32 v87, v34
	v_pk_mov_b32 v[70:71], v[36:37], v[68:69] op_sel:[1,0]
	v_mov_b32_e32 v37, v69
	v_pk_mul_f32 v[68:69], v[90:91], v[90:91]
	v_pk_mul_f32 v[34:35], v[86:87], v[86:87]
	v_pk_add_f32 v[36:37], v[70:71], v[36:37]
	v_pk_mov_b32 v[70:71], v[34:35], v[68:69] op_sel:[1,0]
	v_mov_b32_e32 v35, v69
	v_pk_add_f32 v[34:35], v[70:71], v[34:35]
	v_fmac_f32_e32 v42, 0xba800000, v39
	v_pk_add_f32 v[34:35], v[34:35], v[34:35] op_sel_hi:[0,1]
	v_fmac_f32_e32 v43, 0xba800000, v39
	v_fmac_f32_e32 v40, 0xba800000, v39
	v_mul_f32_e32 v34, v42, v42
	v_fmac_f32_e32 v41, 0xba800000, v39
	v_pk_fma_f32 v[68:69], v[42:43], v[42:43], v[34:35] op_sel_hi:[1,1,0]
	v_mul_f32_e32 v34, v40, v40
	v_pk_add_f32 v[36:37], v[36:37], v[36:37] op_sel_hi:[0,1]
	v_pk_fma_f32 v[70:71], v[40:41], v[40:41], v[34:35] op_sel_hi:[1,1,0]
	v_fmac_f32_e32 v48, 0xba800000, v39
	v_fmac_f32_e32 v46, 0xba800000, v39
	v_fmac_f32_e32 v38, 0xba800000, v39
	v_fmac_f32_e32 v44, 0xba800000, v39
	v_mul_f32_e32 v68, v44, v44
	v_mul_f32_e32 v70, v38, v38
	v_mul_f32_e32 v36, v46, v46
	v_mul_f32_e32 v34, v48, v48
	v_pk_add_f32 v[68:69], v[68:69], v[70:71]
	v_pk_add_f32 v[34:35], v[36:37], v[34:35]
	v_mov_b32_e32 v47, v48
	v_pk_add_f32 v[34:35], v[68:69], v[34:35]
	s_nop 0
	v_add_f32_e32 v34, v34, v35
	s_nop 1
	v_add_f32_dpp v34, v34, v34 quad_perm:[1,0,3,2] row_mask:0xf bank_mask:0xf bound_ctrl:1
	s_nop 1
	v_add_f32_dpp v34, v34, v34 quad_perm:[2,3,0,1] row_mask:0xf bank_mask:0xf bound_ctrl:1
	s_nop 1
	v_add_f32_dpp v34, v34, v34 row_half_mirror row_mask:0xf bank_mask:0xf bound_ctrl:1
	s_nop 1
	v_add_f32_dpp v34, v34, v34 row_mirror row_mask:0xf bank_mask:0xf bound_ctrl:1
	s_nop 0
	v_readlane_b32 s19, v34, 16
	v_readlane_b32 s20, v34, 48
	v_readlane_b32 s0, v34, 0
	v_readlane_b32 s1, v34, 32
	v_mov_b32_e32 v34, s19
	v_mov_b32_e32 v35, s20
	v_pk_add_f32 v[34:35], s[0:1], v[34:35]
	s_ashr_i32 s19, s18, 31
	v_add_f32_e32 v34, v34, v35
	v_fmamk_f32 v34, v34, 0x3a800000, v80
	v_mul_f32_e32 v35, 0x4f800000, v34
	v_cmp_gt_f32_e32 vcc, s7, v34
	s_lshl_b64 s[0:1], s[18:19], 11
	s_and_b32 s20, s36, 3
	v_cndmask_b32_e32 v36, v34, v35, vcc
	v_lshl_add_u64 v[34:35], v[54:55], 0, s[0:1]
	global_load_dwordx2 v[68:69], v[34:35], off
	global_load_dwordx2 v[70:71], v[34:35], off offset:512
	global_load_dwordx2 v[72:73], v[34:35], off offset:1024
	global_load_dwordx2 v[74:75], v[34:35], off offset:1536
	v_sqrt_f32_e32 v37, v36
	s_mul_i32 s30, s20, 0x810
	s_add_i32 s30, s87, s30
	v_add_u32_e32 v39, -1, v37
	v_fma_f32 v45, -v39, v37, v36
	v_cmp_ge_f32_e64 s[18:19], 0, v45
	v_add_u32_e32 v45, 1, v37
	s_nop 0
	v_cndmask_b32_e64 v39, v37, v39, s[18:19]
	v_fma_f32 v37, -v45, v37, v36
	v_cmp_lt_f32_e64 s[18:19], 0, v37
	s_nop 1
	v_cndmask_b32_e64 v37, v39, v45, s[18:19]
	v_mul_f32_e32 v39, 0x37800000, v37
	v_cndmask_b32_e32 v37, v37, v39, vcc
	v_cmp_class_f32_e32 vcc, v36, v81
	s_add_i32 s18, s4, s34
	s_ashr_i32 s19, s18, 31
	v_cndmask_b32_e32 v36, v37, v36, vcc
	v_div_scale_f32 v37, s[0:1], v36, v36, 1.0
	v_rcp_f32_e32 v39, v37
	s_lshl_b64 s[0:1], s[18:19], 11
	v_fma_f32 v34, -v37, v39, 1.0
	v_fmac_f32_e32 v39, v34, v39
	v_div_scale_f32 v34, vcc, 1.0, v36, 1.0
	v_mul_f32_e32 v35, v34, v39
	v_fma_f32 v45, -v37, v35, v34
	v_fmac_f32_e32 v35, v45, v39
	v_fma_f32 v34, -v37, v35, v34
	v_div_fmas_f32 v34, v34, v39, v35
	v_div_fixup_f32 v34, v34, v36, 1.0
	v_mov_b32_e32 v45, v38
	v_pk_mul_f32 v[36:37], v[84:85], v[34:35] op_sel_hi:[1,0]
	v_pk_mul_f32 v[84:85], v[88:89], v[34:35] op_sel_hi:[1,0]
	v_pk_mul_f32 v[38:39], v[44:45], v[34:35] op_sel_hi:[1,0]
	v_mov_b32_e32 v44, v150
	v_pk_fma_f32 v[84:85], v[4:5], v[84:85], v[12:13]
	v_pk_fma_f32 v[36:37], v[2:3], v[36:37], v[10:11]
	v_pk_mul_f32 v[86:87], v[86:87], v[34:35] op_sel_hi:[1,0]
	v_pk_mul_f32 v[88:89], v[90:91], v[34:35] op_sel_hi:[1,0]
	v_pk_fma_f32 v[86:87], v[6:7], v[86:87], v[14:15]
	v_pk_fma_f32 v[88:89], v[8:9], v[88:89], v[16:17]
	v_pk_mul_f32 v[42:43], v[42:43], v[34:35] op_sel_hi:[1,0]
	v_pk_mul_f32 v[40:41], v[40:41], v[34:35] op_sel_hi:[1,0]
	v_pk_mul_f32 v[34:35], v[46:47], v[34:35] op_sel_hi:[1,0]
	v_lshl_add_u32 v48, v44, 3, s30
	v_cvt_pk_bf16_f32 v44, v36, v37
	v_cvt_pk_bf16_f32 v45, v84, v85
	v_lshl_add_u64 v[46:47], v[56:57], 0, s[0:1]
	v_pk_fma_f32 v[40:41], v[20:21], v[40:41], v[28:29]
	v_pk_fma_f32 v[42:43], v[18:19], v[42:43], v[26:27]
	global_store_dwordx2 v[46:47], v[44:45], off
	ds_write_b64 v48, v[44:45] offset:33024
	v_cvt_pk_bf16_f32 v44, v86, v87
	v_cvt_pk_bf16_f32 v45, v88, v89
	v_pk_fma_f32 v[34:35], v[24:25], v[34:35], v[32:33]
	v_pk_fma_f32 v[38:39], v[22:23], v[38:39], v[30:31]
	global_store_dwordx2 v[46:47], v[44:45], off offset:512
	ds_write_b64 v48, v[44:45] offset:33536
	v_cvt_pk_bf16_f32 v44, v42, v43
	v_cvt_pk_bf16_f32 v45, v40, v41
	global_store_dwordx2 v[46:47], v[44:45], off offset:1024
	ds_write_b64 v48, v[44:45] offset:34048
	v_cvt_pk_bf16_f32 v44, v38, v39
	v_cvt_pk_bf16_f32 v45, v34, v35
	global_store_dwordx2 v[46:47], v[44:45], off offset:1536
	ds_write_b64 v48, v[44:45] offset:34560
	v_med3_f32 v36, v36, s38, v82
	v_med3_f32 v37, v37, s38, v82
	v_mov_b32_e32 v44, 0
	v_cvt_pk_fp8_f32 v44, v36, v37
	v_med3_f32 v36, v84, s38, v82
	v_med3_f32 v37, v85, s38, v82
	v_med3_f32 v45, v86, s38, v82
	v_cvt_pk_fp8_f32 v44, v36, v37 op_sel:[0,0,1]
	v_med3_f32 v46, v87, s38, v82
	v_mov_b32_e32 v47, 0
	v_cvt_pk_fp8_f32 v47, v45, v46
	s_lshl_b64 s[0:1], s[18:19], 10
	v_lshl_add_u64 v[36:37], v[58:59], 0, s[0:1]
	global_store_dword v[36:37], v44, off
	v_med3_f32 v44, v88, s38, v82
	v_med3_f32 v45, v89, s38, v82
	v_cvt_pk_fp8_f32 v47, v44, v45 op_sel:[0,0,1]
	v_med3_f32 v42, v42, s38, v82
	v_med3_f32 v43, v43, s38, v82
	v_mov_b32_e32 v44, 0
	v_cvt_pk_fp8_f32 v44, v42, v43
	v_med3_f32 v38, v38, s38, v82
	v_med3_f32 v39, v39, s38, v82
	v_mov_b32_e32 v42, 0
	v_cvt_pk_fp8_f32 v42, v38, v39
	v_med3_f32 v34, v34, s38, v82
	v_med3_f32 v35, v35, s38, v82
	v_med3_f32 v40, v40, s38, v82
	v_med3_f32 v41, v41, s38, v82
	v_cvt_pk_fp8_f32 v42, v34, v35 op_sel:[0,0,1]
	v_cvt_pk_fp8_f32 v44, v40, v41 op_sel:[0,0,1]
	s_cmp_lg_u32 s20, 3
	global_store_dword v[36:37], v47, off offset:256
	global_store_dword v[36:37], v44, off offset:512
	global_store_dword v[36:37], v42, off offset:768
	s_cbranch_scc1 .LBB0_457
	v_mov_b32_e32 v100, v150
	s_nop 0
	v_and_b32_e32 v34, 3, v100
	v_mul_u32_u24_e32 v34, 0x810, v34
	v_and_b32_e32 v38, -16, v100
	v_add3_u32 v83, s87, v34, v38
	ds_read_b128 v[34:37], v83 offset:33024
	v_and_b32_e32 v39, 15, v100
	v_mul_u32_u24_e32 v39, 0x810, v39
	v_add3_u32 v101, 0, v39, v38
	ds_read_b128 v[38:41], v83 offset:33088
	ds_read_b128 v[42:45], v101
	ds_read_b128 v[46:49], v101 offset:64
	s_waitcnt lgkmcnt(0)
	v_mfma_f32_16x16x32_bf16 v[38:41], v[38:41], v[46:49], 0
	v_cmp_gt_i32_e32 vcc, 16, v100
	v_mfma_f32_16x16x32_bf16 v[34:37], v[34:37], v[42:45], 0
	ds_read_b128 v[42:45], v83 offset:33152
	ds_read_b128 v[46:49], v83 offset:33216
	ds_read_b128 v[84:87], v101 offset:128
	ds_read_b128 v[88:91], v101 offset:192
	s_waitcnt lgkmcnt(0)
	v_mfma_f32_16x16x32_bf16 v[42:45], v[42:45], v[84:87], 0
	ds_read_b128 v[84:87], v83 offset:33280
	v_mfma_f32_16x16x32_bf16 v[46:49], v[46:49], v[88:91], 0
	ds_read_b128 v[88:91], v83 offset:33344
	ds_read_b128 v[92:95], v101 offset:256
	ds_read_b128 v[96:99], v101 offset:320
	s_waitcnt lgkmcnt(0)
	v_mfma_f32_16x16x32_bf16 v[34:37], v[84:87], v[92:95], v[34:37]
	ds_read_b128 v[84:87], v83 offset:33408
	v_mfma_f32_16x16x32_bf16 v[38:41], v[88:91], v[96:99], v[38:41]
	ds_read_b128 v[88:91], v83 offset:33472
	ds_read_b128 v[92:95], v101 offset:384
	ds_read_b128 v[96:99], v101 offset:448
	s_waitcnt lgkmcnt(0)
	v_mfma_f32_16x16x32_bf16 v[42:45], v[84:87], v[92:95], v[42:45]
	ds_read_b128 v[84:87], v83 offset:33536
	v_mfma_f32_16x16x32_bf16 v[46:49], v[88:91], v[96:99], v[46:49]
	ds_read_b128 v[88:91], v83 offset:33600
	ds_read_b128 v[92:95], v101 offset:512
	ds_read_b128 v[96:99], v101 offset:576
	s_waitcnt lgkmcnt(0)
	v_mfma_f32_16x16x32_bf16 v[34:37], v[84:87], v[92:95], v[34:37]
	ds_read_b128 v[84:87], v83 offset:33664
	v_mfma_f32_16x16x32_bf16 v[38:41], v[88:91], v[96:99], v[38:41]
	ds_read_b128 v[88:91], v83 offset:33728
	ds_read_b128 v[92:95], v101 offset:640
	ds_read_b128 v[96:99], v101 offset:704
	s_waitcnt lgkmcnt(0)
	v_mfma_f32_16x16x32_bf16 v[42:45], v[84:87], v[92:95], v[42:45]
	ds_read_b128 v[84:87], v83 offset:33792
	ds_read_b128 v[92:95], v83 offset:33856
	v_mfma_f32_16x16x32_bf16 v[46:49], v[88:91], v[96:99], v[46:49]
	ds_read_b128 v[88:91], v101 offset:768
	ds_read_b128 v[96:99], v101 offset:832
	s_waitcnt lgkmcnt(0)
	v_mfma_f32_16x16x32_bf16 v[34:37], v[84:87], v[88:91], v[34:37]
	ds_read_b128 v[84:87], v83 offset:33920
	ds_read_b128 v[88:91], v83 offset:33984
	v_mfma_f32_16x16x32_bf16 v[38:41], v[92:95], v[96:99], v[38:41]
	ds_read_b128 v[92:95], v101 offset:896
	ds_read_b128 v[96:99], v101 offset:960
	s_waitcnt lgkmcnt(0)
	v_mfma_f32_16x16x32_bf16 v[42:45], v[84:87], v[92:95], v[42:45]
	ds_read_b128 v[84:87], v83 offset:34048
	ds_read_b128 v[92:95], v83 offset:34112
	v_mfma_f32_16x16x32_bf16 v[46:49], v[88:91], v[96:99], v[46:49]
	ds_read_b128 v[88:91], v101 offset:1024
	ds_read_b128 v[96:99], v101 offset:1088
	s_waitcnt lgkmcnt(0)
	v_mfma_f32_16x16x32_bf16 v[34:37], v[84:87], v[88:91], v[34:37]
	ds_read_b128 v[84:87], v83 offset:34176
	ds_read_b128 v[88:91], v83 offset:34240
	v_mfma_f32_16x16x32_bf16 v[38:41], v[92:95], v[96:99], v[38:41]
	ds_read_b128 v[92:95], v101 offset:1152
	ds_read_b128 v[96:99], v101 offset:1216
	s_waitcnt lgkmcnt(0)
	v_mfma_f32_16x16x32_bf16 v[42:45], v[84:87], v[92:95], v[42:45]
	ds_read_b128 v[84:87], v83 offset:34304
	ds_read_b128 v[92:95], v83 offset:34368
	v_mfma_f32_16x16x32_bf16 v[46:49], v[88:91], v[96:99], v[46:49]
	ds_read_b128 v[88:91], v101 offset:1280
	ds_read_b128 v[96:99], v101 offset:1344
	s_waitcnt lgkmcnt(0)
	v_mfma_f32_16x16x32_bf16 v[34:37], v[84:87], v[88:91], v[34:37]
	ds_read_b128 v[84:87], v83 offset:34432
	ds_read_b128 v[88:91], v83 offset:34496
	v_mfma_f32_16x16x32_bf16 v[38:41], v[92:95], v[96:99], v[38:41]
	ds_read_b128 v[92:95], v101 offset:1408
	ds_read_b128 v[96:99], v101 offset:1472
	s_waitcnt lgkmcnt(0)
	v_mfma_f32_16x16x32_bf16 v[42:45], v[84:87], v[92:95], v[42:45]
	ds_read_b128 v[84:87], v83 offset:34560
	ds_read_b128 v[92:95], v83 offset:34624
	v_mfma_f32_16x16x32_bf16 v[46:49], v[88:91], v[96:99], v[46:49]
	ds_read_b128 v[88:91], v101 offset:1536
	ds_read_b128 v[96:99], v101 offset:1600
	s_waitcnt lgkmcnt(0)
	v_mfma_f32_16x16x32_bf16 v[34:37], v[84:87], v[88:91], v[34:37]
	ds_read_b128 v[84:87], v83 offset:34688
	ds_read_b128 v[88:91], v83 offset:34752
	v_mfma_f32_16x16x32_bf16 v[38:41], v[92:95], v[96:99], v[38:41]
	ds_read_b128 v[92:95], v101 offset:1664
	ds_read_b128 v[96:99], v101 offset:1728
	s_waitcnt lgkmcnt(0)
	v_mfma_f32_16x16x32_bf16 v[42:45], v[84:87], v[92:95], v[42:45]
	ds_read_b128 v[84:87], v83 offset:34816
	ds_read_b128 v[92:95], v83 offset:34880
	v_mfma_f32_16x16x32_bf16 v[46:49], v[88:91], v[96:99], v[46:49]
	ds_read_b128 v[88:91], v101 offset:1792
	ds_read_b128 v[96:99], v101 offset:1856
	s_waitcnt lgkmcnt(0)
	v_mfma_f32_16x16x32_bf16 v[34:37], v[84:87], v[88:91], v[34:37]
	ds_read_b128 v[84:87], v83 offset:34944
	ds_read_b128 v[88:91], v83 offset:35008
	v_mfma_f32_16x16x32_bf16 v[38:41], v[92:95], v[96:99], v[38:41]
	ds_read_b128 v[92:95], v101 offset:1920
	ds_read_b128 v[96:99], v101 offset:1984
	v_ashrrev_i32_e32 v101, 31, v100
	s_waitcnt lgkmcnt(0)
	v_mfma_f32_16x16x32_bf16 v[42:45], v[84:87], v[92:95], v[42:45]
	s_nop 2
	v_add_f32_e64 v34, v34, v38
	v_add_f32_e64 v35, v35, v39
	v_mfma_f32_16x16x32_bf16 v[46:49], v[88:91], v[96:99], v[46:49]
	s_nop 7
	v_pk_add_f32 v[38:39], v[42:43], v[46:47]
	s_nop 0
	v_pk_add_f32 v[38:39], v[34:35], v[38:39]
	s_nop 1
	v_mov_b32_dpp v34, v38 quad_perm:[1,0,3,2] row_mask:0xf bank_mask:0xf bound_ctrl:1
	v_max_f32_e32 v34, v34, v34
	v_max_f32_e32 v34, v38, v34
	s_nop 1
	v_mov_b32_dpp v35, v34 quad_perm:[2,3,0,1] row_mask:0xf bank_mask:0xf bound_ctrl:1
	v_max_f32_e32 v35, v35, v35
	v_max_f32_e32 v34, v34, v35
	s_nop 1
	v_mov_b32_dpp v35, v34 row_half_mirror row_mask:0xf bank_mask:0xf bound_ctrl:1
	v_max_f32_e32 v35, v35, v35
	v_max_f32_e32 v34, v34, v35
	s_nop 1
	v_mov_b32_dpp v35, v34 row_mirror row_mask:0xf bank_mask:0xf bound_ctrl:1
	v_max_f32_e32 v35, v35, v35
	v_max_f32_e32 v34, v34, v35
	v_sub_f32_e32 v34, v38, v34
	v_mul_f32_e32 v34, 0x3fb8aa3b, v34
	v_exp_f32_e32 v38, v34
	v_lshlrev_b64 v[34:35], 13, v[100:101]
	v_lshl_add_u64 v[34:35], s[26:27], 0, v[34:35]
	v_add_f32_dpp v42, v38, v38 quad_perm:[1,0,3,2] row_mask:0xf bank_mask:0xf bound_ctrl:1
	s_nop 1
	v_add_f32_dpp v42, v42, v42 quad_perm:[2,3,0,1] row_mask:0xf bank_mask:0xf bound_ctrl:1
	s_nop 1
	v_add_f32_dpp v42, v42, v42 row_half_mirror row_mask:0xf bank_mask:0xf bound_ctrl:1
	s_nop 1
	v_mov_b32_dpp v43, v42 row_mirror row_mask:0xf bank_mask:0xf bound_ctrl:1
	s_and_saveexec_b64 s[30:31], vcc
	s_cbranch_execz .LBB0_461
	v_add_f32_e32 v42, v42, v43
	v_rcp_f32_e32 v42, v42
	s_sub_i32 s19, s18, 24
	s_ashr_i32 s0, s19, 11
	s_ashr_i32 s1, s0, 31
	s_and_b32 s19, s19, 0x7ff
	s_lshl_b64 s[0:1], s[0:1], 17
	v_mul_f32_e32 v38, v38, v42
	v_lshl_add_u64 v[42:43], v[34:35], 0, s[0:1]
	s_lshl_b32 s20, s19, 2
	v_lshl_add_u64 v[42:43], v[42:43], 0, s[20:21]
	global_store_dword v[42:43], v38, off

.LBB0_521:
	s_or_b64 exec, exec, s[30:31]
	v_cndmask_b32_e64 v2, -1, v3, s[50:51]
	v_cndmask_b32_e64 v12, -1, v5, s[56:57]
	v_cndmask_b32_e64 v3, -1, v6, s[58:59]
	v_cndmask_b32_e64 v6, -1, v7, s[52:53]
	v_cndmask_b32_e64 v4, -1, v8, s[46:47]
	v_cndmask_b32_e64 v7, -1, v9, s[42:43]
	v_cndmask_b32_e64 v5, -1, v10, s[38:39]
	v_cndmask_b32_e64 v8, -1, v11, s[28:29]
	s_add_i32 s5, s5, s90
	v_perm_b32 v5, v8, v5, s4
	v_perm_b32 v4, v7, v4, s4
	v_perm_b32 v3, v6, v3, s4
	v_perm_b32 v2, v12, v2, s4
	v_lshl_add_u64 v[6:7], v[18:19], 1, v[16:17]
	s_cmpk_lt_i32 s5, 0x200
	global_store_dwordx4 v[6:7], v[2:5], off
	s_waitcnt lgkmcnt(0)
	s_barrier
	s_cbranch_scc0 .LBB0_569
.LBB0_522:
	v_add_u32_e32 v22, s5, v24
	v_ashrrev_i32_e32 v23, 31, v22
	v_lshlrev_b64 v[2:3], 13, v[22:23]
	v_lshl_add_u64 v[2:3], v[14:15], 0, v[2:3]
	global_load_dwordx4 v[6:9], v[2:3], off
	s_nop 0
	global_load_dwordx4 v[2:5], v[2:3], off offset:16
	v_lshlrev_b64 v[18:19], 11, v[22:23]
	v_mov_b32_e32 v21, 0x100
	s_mov_b32 s0, 24
	v_mov_b32_e32 v20, 0
	s_mov_b32 s1, 0
	s_branch .LBB0_525

.LBB0_551:
	s_or_b64 exec, exec, s[62:63]
	v_sub_u32_e32 v2, v3, v2
	s_waitcnt lgkmcnt(0)
	v_add_u32_e32 v2, v2, v5
	v_add3_u32 v5, v2, v4, v6
	v_lshlrev_b32_e32 v4, 5, v22
	v_ashrrev_i32_e32 v3, 4, v22
	v_and_b32_e32 v4, 0x1e0, v4
	v_cmp_lt_i32_sdwa s[0:1], v5, v21 src0_sel:WORD_1 src1_sel:DWORD
	v_lshl_or_b32 v2, v3, 11, v28
	v_add_lshl_u32 v4, v4, v3, 8
	s_and_b64 s[0:1], s[56:57], s[0:1]
	v_min_i32_sdwa v3, v5, v21 dst_sel:DWORD dst_unused:UNUSED_PAD src0_sel:WORD_1 src1_sel:DWORD
	s_or_b64 s[50:51], s[50:51], s[0:1]
	v_add_u32_sdwa v3, v3, v5 dst_sel:DWORD dst_unused:UNUSED_PAD src0_sel:DWORD src1_sel:WORD_0
	s_and_saveexec_b64 s[62:63], s[50:51]
	s_cbranch_execz .LBB0_553
	v_add_u32_e32 v6, v3, v4
	v_ashrrev_i32_e32 v7, 31, v6
	v_lshl_add_u64 v[6:7], v[6:7], 2, s[66:67]
	global_store_dword v[6:7], v2, off
.LBB0_553:
	s_or_b64 exec, exec, s[62:63]
	v_cndmask_b32_e64 v7, 0, 1, s[56:57]
	v_add_u32_sdwa v7, v5, v7 dst_sel:DWORD dst_unused:UNUSED_PAD src0_sel:WORD_1 src1_sel:DWORD
	v_cmp_lt_i32_e64 s[56:57], v7, v21
	v_add_u32_sdwa v6, v5, v10 dst_sel:DWORD dst_unused:UNUSED_PAD src0_sel:WORD_0 src1_sel:DWORD
	s_and_b64 s[0:1], s[58:59], s[56:57]
	v_min_i32_e32 v5, v7, v21
	s_or_b64 s[56:57], s[60:61], s[0:1]
	v_add_u32_e32 v5, v5, v6
	s_and_saveexec_b64 s[62:63], s[56:57]
	s_cbranch_execz .LBB0_555
	v_add_u32_e32 v8, v5, v4
	v_ashrrev_i32_e32 v9, 31, v8
	v_lshl_add_u64 v[8:9], v[8:9], 2, s[66:67]
	v_or_b32_e32 v10, 1, v2
	global_store_dword v[8:9], v10, off
.LBB0_555:
	s_or_b64 exec, exec, s[62:63]
	v_cndmask_b32_e64 v8, 0, 1, s[60:61]
	v_add_u32_e32 v8, v6, v8
	v_cndmask_b32_e64 v6, 0, 1, s[58:59]
	v_add_u32_e32 v7, v7, v6
	v_cmp_lt_i32_e64 s[58:59], v7, v21
	s_and_b64 s[0:1], s[52:53], s[58:59]
	v_min_i32_e32 v6, v7, v21
	s_or_b64 s[58:59], s[54:55], s[0:1]
	v_add_u32_e32 v6, v6, v8
	s_and_saveexec_b64 s[60:61], s[58:59]
	s_cbranch_execz .LBB0_557
	v_add_u32_e32 v10, v6, v4
	v_ashrrev_i32_e32 v11, 31, v10
	v_lshl_add_u64 v[10:11], v[10:11], 2, s[66:67]
	v_or_b32_e32 v9, 2, v2
	global_store_dword v[10:11], v9, off
.LBB0_557:
	s_or_b64 exec, exec, s[60:61]
	v_cndmask_b32_e64 v9, 0, 1, s[54:55]
	v_add_u32_e32 v8, v8, v9
	v_cndmask_b32_e64 v9, 0, 1, s[52:53]
	v_add_u32_e32 v9, v7, v9
	v_cmp_lt_i32_e64 s[52:53], v9, v21
	s_and_b64 s[0:1], s[46:47], s[52:53]
	v_min_i32_e32 v7, v9, v21
	s_or_b64 s[52:53], s[48:49], s[0:1]
	v_add_u32_e32 v7, v7, v8
	s_and_saveexec_b64 s[54:55], s[52:53]
	s_cbranch_execz .LBB0_559
	v_add_u32_e32 v10, v7, v4
	v_ashrrev_i32_e32 v11, 31, v10
	v_lshl_add_u64 v[10:11], v[10:11], 2, s[66:67]
	v_or_b32_e32 v12, 3, v2
	global_store_dword v[10:11], v12, off
.LBB0_559:
	s_or_b64 exec, exec, s[54:55]
	v_cndmask_b32_e64 v10, 0, 1, s[48:49]
	v_add_u32_e32 v10, v8, v10
	v_cndmask_b32_e64 v8, 0, 1, s[46:47]
	v_add_u32_e32 v9, v9, v8
	v_cmp_lt_i32_e64 s[46:47], v9, v21
	s_and_b64 s[0:1], s[42:43], s[46:47]
	v_min_i32_e32 v8, v9, v21
	s_or_b64 s[46:47], s[44:45], s[0:1]
	v_add_u32_e32 v8, v8, v10
	s_and_saveexec_b64 s[48:49], s[46:47]
	s_cbranch_execz .LBB0_561
	v_add_u32_e32 v22, v8, v4
	v_ashrrev_i32_e32 v23, 31, v22
	v_lshl_add_u64 v[22:23], v[22:23], 2, s[66:67]
	v_or_b32_e32 v11, 4, v2
	global_store_dword v[22:23], v11, off
.LBB0_561:
	s_or_b64 exec, exec, s[48:49]
	v_cndmask_b32_e64 v11, 0, 1, s[44:45]
	v_add_u32_e32 v10, v10, v11
	v_cndmask_b32_e64 v11, 0, 1, s[42:43]
	v_add_u32_e32 v12, v9, v11
	v_cmp_lt_i32_e64 s[42:43], v12, v21
	s_and_b64 s[0:1], s[38:39], s[42:43]
	v_min_i32_e32 v9, v12, v21
	s_or_b64 s[42:43], s[40:41], s[0:1]
	v_add_u32_e32 v9, v9, v10
	s_and_saveexec_b64 s[44:45], s[42:43]
	s_cbranch_execz .LBB0_563
	v_add_u32_e32 v22, v9, v4
	v_ashrrev_i32_e32 v23, 31, v22
	v_lshl_add_u64 v[22:23], v[22:23], 2, s[66:67]
	v_or_b32_e32 v11, 5, v2
	global_store_dword v[22:23], v11, off
.LBB0_563:
	s_or_b64 exec, exec, s[44:45]
	v_cndmask_b32_e64 v11, 0, 1, s[40:41]
	v_add_u32_e32 v11, v10, v11
	v_cndmask_b32_e64 v10, 0, 1, s[38:39]
	v_add_u32_e32 v12, v12, v10
	v_cmp_lt_i32_e64 s[38:39], v12, v21
	s_and_b64 s[0:1], s[28:29], s[38:39]
	v_min_i32_e32 v10, v12, v21
	s_or_b64 s[38:39], s[34:35], s[0:1]
	v_add_u32_e32 v10, v10, v11
	s_and_saveexec_b64 s[40:41], s[38:39]
	s_cbranch_execz .LBB0_565
	v_add_u32_e32 v22, v10, v4
	v_ashrrev_i32_e32 v23, 31, v22
	v_lshl_add_u64 v[22:23], v[22:23], 2, s[66:67]
	v_or_b32_e32 v20, 6, v2
	global_store_dword v[22:23], v20, off
.LBB0_565:
	s_or_b64 exec, exec, s[40:41]
	v_cndmask_b32_e64 v22, 0, 1, s[28:29]
	v_add_u32_e32 v12, v12, v22
	v_cmp_lt_i32_e64 s[28:29], v12, v21
	v_cndmask_b32_e64 v20, 0, 1, s[34:35]
	s_and_b64 s[0:1], s[30:31], s[28:29]
	v_min_i32_e32 v12, v12, v21
	s_or_b64 s[28:29], s[36:37], s[0:1]
	v_add3_u32 v11, v11, v20, v12
	s_and_saveexec_b64 s[30:31], s[28:29]
	s_cbranch_execz .LBB0_521
	v_add_u32_e32 v20, v11, v4
	v_ashrrev_i32_e32 v21, 31, v20
	v_lshl_add_u64 v[20:21], v[20:21], 2, s[66:67]
	v_or_b32_e32 v2, 7, v2
	global_store_dword v[20:21], v2, off
	s_branch .LBB0_521

.LBB0_625:
	s_sub_i32 s0, 0x200, s38
	s_min_i32 s41, s0, s90
	s_lshl_b32 s22, s41, 3
	s_ashr_i32 s23, s22, 31
	v_mov_b32_e32 v2, v0
	s_cmp_lt_i32 s2, s22
	s_cselect_b64 s[12:13], -1, 0
	s_cmp_ge_i32 s2, s22
	v_readfirstlane_b32 s42, v2
	s_cbranch_scc1 .LBB0_673
	s_movk_i32 s0, 0xff
	v_cmp_lt_i32_e64 s[8:9], s0, v2
	s_movk_i32 s0, 0x100
	v_lshl_add_u32 v3, v2, 2, s95
	v_cmp_gt_i32_e64 s[10:11], s0, v2
	s_and_saveexec_b64 s[24:25], s[10:11]
	s_cbranch_execz .LBB0_628
	s_or_b32 s0, s41, s80
	s_mul_i32 s0, s0, s76
	s_add_i32 s0, s0, s91
	s_ashr_i32 s1, s0, 31
	s_lshr_b32 s1, s1, 26
	s_add_i32 s1, s0, s1
	s_ashr_i32 s26, s1, 6
	s_lshl_b32 s26, s26, 3
	s_sub_i32 s27, s41, s26
	s_min_i32 s27, s27, 8
	s_abs_i32 s27, s27
	v_cvt_f32_u32_e32 v4, s27
	s_sub_i32 s28, 0, s27
	s_andn2_b32 s1, s1, 63
	s_sub_i32 s0, s0, s1
	v_rcp_iflag_f32_e32 v4, v4
	s_ashr_i32 s1, s0, 31
	s_abs_i32 s0, s0
	v_mul_f32_e32 v4, 0x4f7ffffe, v4
	v_cvt_u32_f32_e32 v4, v4
	s_nop 0
	v_readfirstlane_b32 s29, v4
	s_mul_i32 s28, s28, s29
	s_mul_hi_u32 s28, s29, s28
	s_add_i32 s29, s29, s28
	s_mul_hi_u32 s28, s0, s29
	s_mul_i32 s28, s28, s27
	s_sub_i32 s0, s0, s28
	s_sub_i32 s28, s0, s27
	s_cmp_ge_u32 s0, s27
	s_cselect_b32 s0, s28, s0
	s_sub_i32 s28, s0, s27
	s_cmp_ge_u32 s0, s27
	s_cselect_b32 s0, s28, s0
	s_xor_b32 s0, s0, s1
	s_sub_i32 s0, s0, s1
	s_add_i32 s1, s26, s38
	s_add_i32 s1, s1, s0
	v_lshl_add_u32 v4, s1, 8, v2
	v_ashrrev_i32_e32 v5, 31, v4
	v_lshl_add_u64 v[4:5], v[4:5], 2, s[16:17]
	global_load_dword v4, v[4:5], off
	s_waitcnt vmcnt(0) lgkmcnt(0)
	v_lshlrev_b32_e32 v4, 10, v4
	ds_write_b32 v3, v4
.LBB0_628:
	s_or_b64 exec, exec, s[24:25]
	v_readlane_b32 s0, v254, 23
	v_mov_b64_e32 v[4:5], s[22:23]
	v_readlane_b32 s1, v254, 24
	s_nop 1
	v_cmp_ge_i64_e32 vcc, s[0:1], v[4:5]
	s_cbranch_vccnz .LBB0_673
	s_and_saveexec_b64 s[24:25], s[10:11]
	s_cbranch_execz .LBB0_631
	v_readlane_b32 s0, v254, 22
	s_or_b32 s0, s41, s0
	v_readlane_b32 s1, v254, 21
	s_mul_i32 s0, s0, s1
	s_add_i32 s0, s0, s89
	s_ashr_i32 s1, s0, 31
	s_lshr_b32 s1, s1, 26
	s_add_i32 s1, s0, s1
	s_ashr_i32 s26, s1, 6
	s_lshl_b32 s26, s26, 3
	s_sub_i32 s27, s41, s26
	s_min_i32 s27, s27, 8
	s_abs_i32 s27, s27
	v_cvt_f32_u32_e32 v4, s27
	s_sub_i32 s28, 0, s27
	s_andn2_b32 s1, s1, 63
	s_sub_i32 s0, s0, s1
	v_rcp_iflag_f32_e32 v4, v4
	s_ashr_i32 s1, s0, 31
	s_abs_i32 s0, s0
	v_mul_f32_e32 v4, 0x4f7ffffe, v4
	v_cvt_u32_f32_e32 v4, v4
	s_nop 0
	v_readfirstlane_b32 s29, v4
	s_mul_i32 s28, s28, s29
	s_mul_hi_u32 s28, s29, s28
	s_add_i32 s29, s29, s28
	s_mul_hi_u32 s28, s0, s29
	s_mul_i32 s28, s28, s27
	s_sub_i32 s0, s0, s28
	s_sub_i32 s28, s0, s27
	s_cmp_ge_u32 s0, s27
	s_cselect_b32 s0, s28, s0
	s_sub_i32 s28, s0, s27
	s_cmp_ge_u32 s0, s27
	s_cselect_b32 s0, s28, s0
	s_xor_b32 s0, s0, s1
	s_sub_i32 s0, s0, s1
	s_add_i32 s1, s26, s38
	s_add_i32 s1, s1, s0
	v_lshl_add_u32 v4, s1, 8, v2
	v_ashrrev_i32_e32 v5, 31, v4
	v_lshl_add_u64 v[4:5], v[4:5], 2, s[16:17]
	global_load_dword v4, v[4:5], off
	s_waitcnt vmcnt(0) lgkmcnt(0)
	v_lshlrev_b32_e32 v4, 10, v4
	ds_write_b32 v3, v4 offset:1024
.LBB0_631:
	s_or_b64 exec, exec, s[24:25]
	v_readlane_b32 s0, v254, 28
	v_mov_b64_e32 v[4:5], s[22:23]
	v_readlane_b32 s1, v254, 29
	s_nop 1
	v_cmp_ge_i64_e32 vcc, s[0:1], v[4:5]
	s_cbranch_vccnz .LBB0_673
	s_and_saveexec_b64 s[24:25], s[10:11]
	s_cbranch_execz .LBB0_634
	v_readlane_b32 s0, v254, 27
	s_or_b32 s0, s41, s0
	v_readlane_b32 s1, v254, 26
	s_mul_i32 s0, s0, s1
	v_readlane_b32 s1, v254, 25
	s_add_i32 s0, s0, s1
	s_ashr_i32 s1, s0, 31
	s_lshr_b32 s1, s1, 26
	s_add_i32 s1, s0, s1
	s_ashr_i32 s26, s1, 6
	s_lshl_b32 s26, s26, 3
	s_sub_i32 s27, s41, s26
	s_min_i32 s27, s27, 8
	s_abs_i32 s27, s27
	v_cvt_f32_u32_e32 v4, s27
	s_sub_i32 s28, 0, s27
	s_andn2_b32 s1, s1, 63
	s_sub_i32 s0, s0, s1
	v_rcp_iflag_f32_e32 v4, v4
	s_ashr_i32 s1, s0, 31
	s_abs_i32 s0, s0
	v_mul_f32_e32 v4, 0x4f7ffffe, v4
	v_cvt_u32_f32_e32 v4, v4
	s_nop 0
	v_readfirstlane_b32 s29, v4
	s_mul_i32 s28, s28, s29
	s_mul_hi_u32 s28, s29, s28
	s_add_i32 s29, s29, s28
	s_mul_hi_u32 s28, s0, s29
	s_mul_i32 s28, s28, s27
	s_sub_i32 s0, s0, s28
	s_sub_i32 s28, s0, s27
	s_cmp_ge_u32 s0, s27
	s_cselect_b32 s0, s28, s0
	s_sub_i32 s28, s0, s27
	s_cmp_ge_u32 s0, s27
	s_cselect_b32 s0, s28, s0
	s_xor_b32 s0, s0, s1
	s_sub_i32 s0, s0, s1
	s_add_i32 s1, s26, s38
	s_add_i32 s1, s1, s0
	v_lshl_add_u32 v4, s1, 8, v2
	v_ashrrev_i32_e32 v5, 31, v4
	v_lshl_add_u64 v[4:5], v[4:5], 2, s[16:17]
	global_load_dword v4, v[4:5], off
	s_waitcnt vmcnt(0) lgkmcnt(0)
	v_lshlrev_b32_e32 v4, 10, v4
	ds_write_b32 v3, v4 offset:2048
.LBB0_634:
	s_or_b64 exec, exec, s[24:25]
	v_readlane_b32 s0, v254, 33
	v_mov_b64_e32 v[4:5], s[22:23]
	v_readlane_b32 s1, v254, 34
	s_nop 1
	v_cmp_ge_i64_e32 vcc, s[0:1], v[4:5]
	s_cbranch_vccnz .LBB0_673
	s_and_saveexec_b64 s[24:25], s[10:11]
	s_cbranch_execz .LBB0_637
	v_readlane_b32 s0, v254, 32
	s_or_b32 s0, s41, s0
	v_readlane_b32 s1, v254, 31
	s_mul_i32 s0, s0, s1
	v_readlane_b32 s1, v254, 30
	s_add_i32 s0, s0, s1
	s_ashr_i32 s1, s0, 31
	s_lshr_b32 s1, s1, 26
	s_add_i32 s1, s0, s1
	s_ashr_i32 s26, s1, 6
	s_lshl_b32 s26, s26, 3
	s_sub_i32 s27, s41, s26
	s_min_i32 s27, s27, 8
	s_abs_i32 s27, s27
	v_cvt_f32_u32_e32 v4, s27
	s_sub_i32 s28, 0, s27
	s_andn2_b32 s1, s1, 63
	s_sub_i32 s0, s0, s1
	v_rcp_iflag_f32_e32 v4, v4
	s_ashr_i32 s1, s0, 31
	s_abs_i32 s0, s0
	v_mul_f32_e32 v4, 0x4f7ffffe, v4
	v_cvt_u32_f32_e32 v4, v4
	s_nop 0
	v_readfirstlane_b32 s29, v4
	s_mul_i32 s28, s28, s29
	s_mul_hi_u32 s28, s29, s28
	s_add_i32 s29, s29, s28
	s_mul_hi_u32 s28, s0, s29
	s_mul_i32 s28, s28, s27
	s_sub_i32 s0, s0, s28
	s_sub_i32 s28, s0, s27
	s_cmp_ge_u32 s0, s27
	s_cselect_b32 s0, s28, s0
	s_sub_i32 s28, s0, s27
	s_cmp_ge_u32 s0, s27
	s_cselect_b32 s0, s28, s0
	s_xor_b32 s0, s0, s1
	s_sub_i32 s0, s0, s1
	s_add_i32 s1, s26, s38
	s_add_i32 s1, s1, s0
	v_lshl_add_u32 v4, s1, 8, v2
	v_ashrrev_i32_e32 v5, 31, v4
	v_lshl_add_u64 v[4:5], v[4:5], 2, s[16:17]
	global_load_dword v4, v[4:5], off
	s_waitcnt vmcnt(0) lgkmcnt(0)
	v_lshlrev_b32_e32 v4, 10, v4
	ds_write_b32 v3, v4 offset:3072
.LBB0_637:
	s_or_b64 exec, exec, s[24:25]
	v_readlane_b32 s0, v254, 38
	v_mov_b64_e32 v[4:5], s[22:23]
	v_readlane_b32 s1, v254, 39
	s_nop 1
	v_cmp_ge_i64_e32 vcc, s[0:1], v[4:5]
	s_cbranch_vccnz .LBB0_673
	s_and_saveexec_b64 s[24:25], s[10:11]
	s_cbranch_execz .LBB0_640
	v_readlane_b32 s0, v254, 37
	s_or_b32 s0, s41, s0
	v_readlane_b32 s1, v254, 36
	s_mul_i32 s0, s0, s1
	v_readlane_b32 s1, v254, 35
	s_add_i32 s0, s0, s1
	s_ashr_i32 s1, s0, 31
	s_lshr_b32 s1, s1, 26
	s_add_i32 s1, s0, s1
	s_ashr_i32 s26, s1, 6
	s_lshl_b32 s26, s26, 3
	s_sub_i32 s27, s41, s26
	s_min_i32 s27, s27, 8
	s_abs_i32 s27, s27
	v_cvt_f32_u32_e32 v4, s27
	s_sub_i32 s28, 0, s27
	s_andn2_b32 s1, s1, 63
	s_sub_i32 s0, s0, s1
	v_rcp_iflag_f32_e32 v4, v4
	s_ashr_i32 s1, s0, 31
	s_abs_i32 s0, s0
	v_mul_f32_e32 v4, 0x4f7ffffe, v4
	v_cvt_u32_f32_e32 v4, v4
	s_nop 0
	v_readfirstlane_b32 s29, v4
	s_mul_i32 s28, s28, s29
	s_mul_hi_u32 s28, s29, s28
	s_add_i32 s29, s29, s28
	s_mul_hi_u32 s28, s0, s29
	s_mul_i32 s28, s28, s27
	s_sub_i32 s0, s0, s28
	s_sub_i32 s28, s0, s27
	s_cmp_ge_u32 s0, s27
	s_cselect_b32 s0, s28, s0
	s_sub_i32 s28, s0, s27
	s_cmp_ge_u32 s0, s27
	s_cselect_b32 s0, s28, s0
	s_xor_b32 s0, s0, s1
	s_sub_i32 s0, s0, s1
	s_add_i32 s1, s26, s38
	s_add_i32 s1, s1, s0
	v_lshl_add_u32 v4, s1, 8, v2
	v_ashrrev_i32_e32 v5, 31, v4
	v_lshl_add_u64 v[4:5], v[4:5], 2, s[16:17]
	global_load_dword v4, v[4:5], off
	s_waitcnt vmcnt(0) lgkmcnt(0)
	v_lshlrev_b32_e32 v4, 10, v4
	ds_write_b32 v3, v4 offset:4096
.LBB0_640:
	s_or_b64 exec, exec, s[24:25]
	v_readlane_b32 s0, v254, 43
	v_mov_b64_e32 v[4:5], s[22:23]
	v_readlane_b32 s1, v254, 44
	s_nop 1
	v_cmp_ge_i64_e32 vcc, s[0:1], v[4:5]
	s_cbranch_vccnz .LBB0_673
	s_and_saveexec_b64 s[24:25], s[10:11]
	s_cbranch_execz .LBB0_643
	v_readlane_b32 s0, v254, 42
	s_or_b32 s0, s41, s0
	v_readlane_b32 s1, v254, 41
	s_mul_i32 s0, s0, s1
	v_readlane_b32 s1, v254, 40
	s_add_i32 s0, s0, s1
	s_ashr_i32 s1, s0, 31
	s_lshr_b32 s1, s1, 26
	s_add_i32 s1, s0, s1
	s_ashr_i32 s26, s1, 6
	s_lshl_b32 s26, s26, 3
	s_sub_i32 s27, s41, s26
	s_min_i32 s27, s27, 8
	s_abs_i32 s27, s27
	v_cvt_f32_u32_e32 v4, s27
	s_sub_i32 s28, 0, s27
	s_andn2_b32 s1, s1, 63
	s_sub_i32 s0, s0, s1
	v_rcp_iflag_f32_e32 v4, v4
	s_ashr_i32 s1, s0, 31
	s_abs_i32 s0, s0
	v_mul_f32_e32 v4, 0x4f7ffffe, v4
	v_cvt_u32_f32_e32 v4, v4
	s_nop 0
	v_readfirstlane_b32 s29, v4
	s_mul_i32 s28, s28, s29
	s_mul_hi_u32 s28, s29, s28
	s_add_i32 s29, s29, s28
	s_mul_hi_u32 s28, s0, s29
	s_mul_i32 s28, s28, s27
	s_sub_i32 s0, s0, s28
	s_sub_i32 s28, s0, s27
	s_cmp_ge_u32 s0, s27
	s_cselect_b32 s0, s28, s0
	s_sub_i32 s28, s0, s27
	s_cmp_ge_u32 s0, s27
	s_cselect_b32 s0, s28, s0
	s_xor_b32 s0, s0, s1
	s_sub_i32 s0, s0, s1
	s_add_i32 s1, s26, s38
	s_add_i32 s1, s1, s0
	v_lshl_add_u32 v4, s1, 8, v2
	v_ashrrev_i32_e32 v5, 31, v4
	v_lshl_add_u64 v[4:5], v[4:5], 2, s[16:17]
	global_load_dword v4, v[4:5], off
	s_waitcnt vmcnt(0) lgkmcnt(0)
	v_lshlrev_b32_e32 v4, 10, v4
	ds_write_b32 v3, v4 offset:5120
.LBB0_643:
	s_or_b64 exec, exec, s[24:25]
	v_readlane_b32 s0, v254, 48
	v_mov_b64_e32 v[4:5], s[22:23]
	v_readlane_b32 s1, v254, 49
	s_nop 1
	v_cmp_ge_i64_e32 vcc, s[0:1], v[4:5]
	s_cbranch_vccnz .LBB0_673
	s_and_saveexec_b64 s[24:25], s[10:11]
	s_cbranch_execz .LBB0_646
	v_readlane_b32 s0, v254, 47
	s_or_b32 s0, s41, s0
	v_readlane_b32 s1, v254, 46
	s_mul_i32 s0, s0, s1
	v_readlane_b32 s1, v254, 45
	s_add_i32 s0, s0, s1
	s_ashr_i32 s1, s0, 31
	s_lshr_b32 s1, s1, 26
	s_add_i32 s1, s0, s1
	s_ashr_i32 s26, s1, 6
	s_lshl_b32 s26, s26, 3
	s_sub_i32 s27, s41, s26
	s_min_i32 s27, s27, 8
	s_abs_i32 s27, s27
	v_cvt_f32_u32_e32 v4, s27
	s_sub_i32 s28, 0, s27
	s_andn2_b32 s1, s1, 63
	s_sub_i32 s0, s0, s1
	v_rcp_iflag_f32_e32 v4, v4
	s_ashr_i32 s1, s0, 31
	s_abs_i32 s0, s0
	v_mul_f32_e32 v4, 0x4f7ffffe, v4
	v_cvt_u32_f32_e32 v4, v4
	s_nop 0
	v_readfirstlane_b32 s29, v4
	s_mul_i32 s28, s28, s29
	s_mul_hi_u32 s28, s29, s28
	s_add_i32 s29, s29, s28
	s_mul_hi_u32 s28, s0, s29
	s_mul_i32 s28, s28, s27
	s_sub_i32 s0, s0, s28
	s_sub_i32 s28, s0, s27
	s_cmp_ge_u32 s0, s27
	s_cselect_b32 s0, s28, s0
	s_sub_i32 s28, s0, s27
	s_cmp_ge_u32 s0, s27
	s_cselect_b32 s0, s28, s0
	s_xor_b32 s0, s0, s1
	s_sub_i32 s0, s0, s1
	s_add_i32 s1, s26, s38
	s_add_i32 s1, s1, s0
	v_lshl_add_u32 v4, s1, 8, v2
	v_ashrrev_i32_e32 v5, 31, v4
	v_lshl_add_u64 v[4:5], v[4:5], 2, s[16:17]
	global_load_dword v4, v[4:5], off
	s_waitcnt vmcnt(0) lgkmcnt(0)
	v_lshlrev_b32_e32 v4, 10, v4
	ds_write_b32 v3, v4 offset:6144
.LBB0_646:
	s_or_b64 exec, exec, s[24:25]
	v_readlane_b32 s0, v254, 53
	v_mov_b64_e32 v[4:5], s[22:23]
	v_readlane_b32 s1, v254, 54
	s_nop 1
	v_cmp_ge_i64_e32 vcc, s[0:1], v[4:5]
	s_cbranch_vccnz .LBB0_673
	s_and_saveexec_b64 s[24:25], s[10:11]
	s_cbranch_execz .LBB0_649
	v_readlane_b32 s0, v254, 52
	s_or_b32 s0, s41, s0
	v_readlane_b32 s1, v254, 51
	s_mul_i32 s0, s0, s1
	v_readlane_b32 s1, v254, 50
	s_add_i32 s0, s0, s1
	s_ashr_i32 s1, s0, 31
	s_lshr_b32 s1, s1, 26
	s_add_i32 s1, s0, s1
	s_ashr_i32 s26, s1, 6
	s_lshl_b32 s26, s26, 3
	s_sub_i32 s27, s41, s26
	s_min_i32 s27, s27, 8
	s_abs_i32 s27, s27
	v_cvt_f32_u32_e32 v4, s27
	s_sub_i32 s28, 0, s27
	s_andn2_b32 s1, s1, 63
	s_sub_i32 s0, s0, s1
	v_rcp_iflag_f32_e32 v4, v4
	s_ashr_i32 s1, s0, 31
	s_abs_i32 s0, s0
	v_mul_f32_e32 v4, 0x4f7ffffe, v4
	v_cvt_u32_f32_e32 v4, v4
	s_nop 0
	v_readfirstlane_b32 s29, v4
	s_mul_i32 s28, s28, s29
	s_mul_hi_u32 s28, s29, s28
	s_add_i32 s29, s29, s28
	s_mul_hi_u32 s28, s0, s29
	s_mul_i32 s28, s28, s27
	s_sub_i32 s0, s0, s28
	s_sub_i32 s28, s0, s27
	s_cmp_ge_u32 s0, s27
	s_cselect_b32 s0, s28, s0
	s_sub_i32 s28, s0, s27
	s_cmp_ge_u32 s0, s27
	s_cselect_b32 s0, s28, s0
	s_xor_b32 s0, s0, s1
	s_sub_i32 s0, s0, s1
	s_add_i32 s1, s26, s38
	s_add_i32 s1, s1, s0
	v_lshl_add_u32 v4, s1, 8, v2
	v_ashrrev_i32_e32 v5, 31, v4
	v_lshl_add_u64 v[4:5], v[4:5], 2, s[16:17]
	global_load_dword v4, v[4:5], off
	s_waitcnt vmcnt(0) lgkmcnt(0)
	v_lshlrev_b32_e32 v4, 10, v4
	ds_write_b32 v3, v4 offset:7168
.LBB0_649:
	s_or_b64 exec, exec, s[24:25]
	v_readlane_b32 s0, v254, 58
	v_mov_b64_e32 v[4:5], s[22:23]
	v_readlane_b32 s1, v254, 59
	s_nop 1
	v_cmp_ge_i64_e32 vcc, s[0:1], v[4:5]
	s_cbranch_vccnz .LBB0_673
	s_and_saveexec_b64 s[24:25], s[10:11]
	s_cbranch_execz .LBB0_652
	v_readlane_b32 s0, v254, 57
	s_or_b32 s0, s41, s0
	v_readlane_b32 s1, v254, 56
	s_mul_i32 s0, s0, s1
	v_readlane_b32 s1, v254, 55
	s_add_i32 s0, s0, s1
	s_ashr_i32 s1, s0, 31
	s_lshr_b32 s1, s1, 26
	s_add_i32 s1, s0, s1
	s_ashr_i32 s26, s1, 6
	s_lshl_b32 s26, s26, 3
	s_sub_i32 s27, s41, s26
	s_min_i32 s27, s27, 8
	s_abs_i32 s27, s27
	v_cvt_f32_u32_e32 v4, s27
	s_sub_i32 s28, 0, s27
	s_andn2_b32 s1, s1, 63
	s_sub_i32 s0, s0, s1
	v_rcp_iflag_f32_e32 v4, v4
	s_ashr_i32 s1, s0, 31
	s_abs_i32 s0, s0
	v_mul_f32_e32 v4, 0x4f7ffffe, v4
	v_cvt_u32_f32_e32 v4, v4
	s_nop 0
	v_readfirstlane_b32 s29, v4
	s_mul_i32 s28, s28, s29
	s_mul_hi_u32 s28, s29, s28
	s_add_i32 s29, s29, s28
	s_mul_hi_u32 s28, s0, s29
	s_mul_i32 s28, s28, s27
	s_sub_i32 s0, s0, s28
	s_sub_i32 s28, s0, s27
	s_cmp_ge_u32 s0, s27
	s_cselect_b32 s0, s28, s0
	s_sub_i32 s28, s0, s27
	s_cmp_ge_u32 s0, s27
	s_cselect_b32 s0, s28, s0
	s_xor_b32 s0, s0, s1
	s_sub_i32 s0, s0, s1
	s_add_i32 s1, s26, s38
	s_add_i32 s1, s1, s0
	v_lshl_add_u32 v4, s1, 8, v2
	v_ashrrev_i32_e32 v5, 31, v4
	v_lshl_add_u64 v[4:5], v[4:5], 2, s[16:17]
	global_load_dword v4, v[4:5], off
	s_waitcnt vmcnt(0) lgkmcnt(0)
	v_lshlrev_b32_e32 v4, 10, v4
	ds_write_b32 v3, v4 offset:8192
.LBB0_652:
	s_or_b64 exec, exec, s[24:25]
	v_readlane_b32 s0, v254, 63
	v_mov_b64_e32 v[4:5], s[22:23]
	v_readlane_b32 s1, v253, 0
	s_nop 1
	v_cmp_ge_i64_e32 vcc, s[0:1], v[4:5]
	s_cbranch_vccnz .LBB0_673
	s_and_saveexec_b64 s[24:25], s[10:11]
	s_cbranch_execz .LBB0_655
	v_readlane_b32 s0, v254, 62
	s_or_b32 s0, s41, s0
	v_readlane_b32 s1, v254, 61
	s_mul_i32 s0, s0, s1
	v_readlane_b32 s1, v254, 60
	s_add_i32 s0, s0, s1
	s_ashr_i32 s1, s0, 31
	s_lshr_b32 s1, s1, 26
	s_add_i32 s1, s0, s1
	s_ashr_i32 s26, s1, 6
	s_lshl_b32 s26, s26, 3
	s_sub_i32 s27, s41, s26
	s_min_i32 s27, s27, 8
	s_abs_i32 s27, s27
	v_cvt_f32_u32_e32 v4, s27
	s_sub_i32 s28, 0, s27
	s_andn2_b32 s1, s1, 63
	s_sub_i32 s0, s0, s1
	v_rcp_iflag_f32_e32 v4, v4
	s_ashr_i32 s1, s0, 31
	s_abs_i32 s0, s0
	v_mul_f32_e32 v4, 0x4f7ffffe, v4
	v_cvt_u32_f32_e32 v4, v4
	s_nop 0
	v_readfirstlane_b32 s29, v4
	s_mul_i32 s28, s28, s29
	s_mul_hi_u32 s28, s29, s28
	s_add_i32 s29, s29, s28
	s_mul_hi_u32 s28, s0, s29
	s_mul_i32 s28, s28, s27
	s_sub_i32 s0, s0, s28
	s_sub_i32 s28, s0, s27
	s_cmp_ge_u32 s0, s27
	s_cselect_b32 s0, s28, s0
	s_sub_i32 s28, s0, s27
	s_cmp_ge_u32 s0, s27
	s_cselect_b32 s0, s28, s0
	s_xor_b32 s0, s0, s1
	s_sub_i32 s0, s0, s1
	s_add_i32 s1, s26, s38
	s_add_i32 s1, s1, s0
	v_lshl_add_u32 v4, s1, 8, v2
	v_ashrrev_i32_e32 v5, 31, v4
	v_lshl_add_u64 v[4:5], v[4:5], 2, s[16:17]
	global_load_dword v4, v[4:5], off
	s_waitcnt vmcnt(0) lgkmcnt(0)
	v_lshlrev_b32_e32 v4, 10, v4
	ds_write_b32 v3, v4 offset:9216
.LBB0_655:
	s_or_b64 exec, exec, s[24:25]
	v_readlane_b32 s0, v253, 4
	v_mov_b64_e32 v[4:5], s[22:23]
	v_readlane_b32 s1, v253, 5
	s_nop 1
	v_cmp_ge_i64_e32 vcc, s[0:1], v[4:5]
	s_cbranch_vccnz .LBB0_673
	s_and_saveexec_b64 s[24:25], s[10:11]
	s_cbranch_execz .LBB0_658
	v_readlane_b32 s0, v253, 3
	s_or_b32 s0, s41, s0
	v_readlane_b32 s1, v253, 2
	s_mul_i32 s0, s0, s1
	v_readlane_b32 s1, v253, 1
	s_add_i32 s0, s0, s1
	s_ashr_i32 s1, s0, 31
	s_lshr_b32 s1, s1, 26
	s_add_i32 s1, s0, s1
	s_ashr_i32 s26, s1, 6
	s_lshl_b32 s26, s26, 3
	s_sub_i32 s27, s41, s26
	s_min_i32 s27, s27, 8
	s_abs_i32 s27, s27
	v_cvt_f32_u32_e32 v4, s27
	s_sub_i32 s28, 0, s27
	s_andn2_b32 s1, s1, 63
	s_sub_i32 s0, s0, s1
	v_rcp_iflag_f32_e32 v4, v4
	s_ashr_i32 s1, s0, 31
	s_abs_i32 s0, s0
	v_mul_f32_e32 v4, 0x4f7ffffe, v4
	v_cvt_u32_f32_e32 v4, v4
	s_nop 0
	v_readfirstlane_b32 s29, v4
	s_mul_i32 s28, s28, s29
	s_mul_hi_u32 s28, s29, s28
	s_add_i32 s29, s29, s28
	s_mul_hi_u32 s28, s0, s29
	s_mul_i32 s28, s28, s27
	s_sub_i32 s0, s0, s28
	s_sub_i32 s28, s0, s27
	s_cmp_ge_u32 s0, s27
	s_cselect_b32 s0, s28, s0
	s_sub_i32 s28, s0, s27
	s_cmp_ge_u32 s0, s27
	s_cselect_b32 s0, s28, s0
	s_xor_b32 s0, s0, s1
	s_sub_i32 s0, s0, s1
	s_add_i32 s1, s26, s38
	s_add_i32 s1, s1, s0
	v_lshl_add_u32 v4, s1, 8, v2
	v_ashrrev_i32_e32 v5, 31, v4
	v_lshl_add_u64 v[4:5], v[4:5], 2, s[16:17]
	global_load_dword v4, v[4:5], off
	s_waitcnt vmcnt(0) lgkmcnt(0)
	v_lshlrev_b32_e32 v4, 10, v4
	ds_write_b32 v3, v4 offset:10240
.LBB0_658:
	s_or_b64 exec, exec, s[24:25]
	v_readlane_b32 s0, v253, 9
	v_mov_b64_e32 v[4:5], s[22:23]
	v_readlane_b32 s1, v253, 10
	s_nop 1
	v_cmp_ge_i64_e32 vcc, s[0:1], v[4:5]
	s_cbranch_vccnz .LBB0_673
	s_and_saveexec_b64 s[24:25], s[10:11]
	s_cbranch_execz .LBB0_661
	v_readlane_b32 s0, v253, 8
	s_or_b32 s0, s41, s0
	v_readlane_b32 s1, v253, 7
	s_mul_i32 s0, s0, s1
	v_readlane_b32 s1, v253, 6
	s_add_i32 s0, s0, s1
	s_ashr_i32 s1, s0, 31
	s_lshr_b32 s1, s1, 26
	s_add_i32 s1, s0, s1
	s_ashr_i32 s26, s1, 6
	s_lshl_b32 s26, s26, 3
	s_sub_i32 s27, s41, s26
	s_min_i32 s27, s27, 8
	s_abs_i32 s27, s27
	v_cvt_f32_u32_e32 v4, s27
	s_sub_i32 s28, 0, s27
	s_andn2_b32 s1, s1, 63
	s_sub_i32 s0, s0, s1
	v_rcp_iflag_f32_e32 v4, v4
	s_ashr_i32 s1, s0, 31
	s_abs_i32 s0, s0
	v_mul_f32_e32 v4, 0x4f7ffffe, v4
	v_cvt_u32_f32_e32 v4, v4
	s_nop 0
	v_readfirstlane_b32 s29, v4
	s_mul_i32 s28, s28, s29
	s_mul_hi_u32 s28, s29, s28
	s_add_i32 s29, s29, s28
	s_mul_hi_u32 s28, s0, s29
	s_mul_i32 s28, s28, s27
	s_sub_i32 s0, s0, s28
	s_sub_i32 s28, s0, s27
	s_cmp_ge_u32 s0, s27
	s_cselect_b32 s0, s28, s0
	s_sub_i32 s28, s0, s27
	s_cmp_ge_u32 s0, s27
	s_cselect_b32 s0, s28, s0
	s_xor_b32 s0, s0, s1
	s_sub_i32 s0, s0, s1
	s_add_i32 s1, s26, s38
	s_add_i32 s1, s1, s0
	v_lshl_add_u32 v4, s1, 8, v2
	v_ashrrev_i32_e32 v5, 31, v4
	v_lshl_add_u64 v[4:5], v[4:5], 2, s[16:17]
	global_load_dword v4, v[4:5], off
	s_waitcnt vmcnt(0) lgkmcnt(0)
	v_lshlrev_b32_e32 v4, 10, v4
	ds_write_b32 v3, v4 offset:11264
.LBB0_661:
	s_or_b64 exec, exec, s[24:25]
	v_readlane_b32 s0, v253, 14
	v_mov_b64_e32 v[4:5], s[22:23]
	v_readlane_b32 s1, v253, 15
	s_nop 1
	v_cmp_ge_i64_e32 vcc, s[0:1], v[4:5]
	s_cbranch_vccnz .LBB0_673
	s_and_saveexec_b64 s[24:25], s[10:11]
	s_cbranch_execz .LBB0_664
	v_readlane_b32 s0, v253, 13
	s_or_b32 s0, s41, s0
	v_readlane_b32 s1, v253, 12
	s_mul_i32 s0, s0, s1
	v_readlane_b32 s1, v253, 11
	s_add_i32 s0, s0, s1
	s_ashr_i32 s1, s0, 31
	s_lshr_b32 s1, s1, 26
	s_add_i32 s1, s0, s1
	s_ashr_i32 s26, s1, 6
	s_lshl_b32 s26, s26, 3
	s_sub_i32 s27, s41, s26
	s_min_i32 s27, s27, 8
	s_abs_i32 s27, s27
	v_cvt_f32_u32_e32 v4, s27
	s_sub_i32 s28, 0, s27
	s_andn2_b32 s1, s1, 63
	s_sub_i32 s0, s0, s1
	v_rcp_iflag_f32_e32 v4, v4
	s_ashr_i32 s1, s0, 31
	s_abs_i32 s0, s0
	v_mul_f32_e32 v4, 0x4f7ffffe, v4
	v_cvt_u32_f32_e32 v4, v4
	s_nop 0
	v_readfirstlane_b32 s29, v4
	s_mul_i32 s28, s28, s29
	s_mul_hi_u32 s28, s29, s28
	s_add_i32 s29, s29, s28
	s_mul_hi_u32 s28, s0, s29
	s_mul_i32 s28, s28, s27
	s_sub_i32 s0, s0, s28
	s_sub_i32 s28, s0, s27
	s_cmp_ge_u32 s0, s27
	s_cselect_b32 s0, s28, s0
	s_sub_i32 s28, s0, s27
	s_cmp_ge_u32 s0, s27
	s_cselect_b32 s0, s28, s0
	s_xor_b32 s0, s0, s1
	s_sub_i32 s0, s0, s1
	s_add_i32 s1, s26, s38
	s_add_i32 s1, s1, s0
	v_lshl_add_u32 v4, s1, 8, v2
	v_ashrrev_i32_e32 v5, 31, v4
	v_lshl_add_u64 v[4:5], v[4:5], 2, s[16:17]
	global_load_dword v4, v[4:5], off
	s_waitcnt vmcnt(0) lgkmcnt(0)
	v_lshlrev_b32_e32 v4, 10, v4
	ds_write_b32 v3, v4 offset:12288
.LBB0_664:
	s_or_b64 exec, exec, s[24:25]
	v_readlane_b32 s0, v253, 19
	v_mov_b64_e32 v[4:5], s[22:23]
	v_readlane_b32 s1, v253, 20
	s_nop 1
	v_cmp_ge_i64_e32 vcc, s[0:1], v[4:5]
	s_cbranch_vccnz .LBB0_673
	s_and_saveexec_b64 s[24:25], s[10:11]
	s_cbranch_execz .LBB0_667
	v_readlane_b32 s0, v253, 18
	s_or_b32 s0, s41, s0
	v_readlane_b32 s1, v253, 17
	s_mul_i32 s0, s0, s1
	v_readlane_b32 s1, v253, 16
	s_add_i32 s0, s0, s1
	s_ashr_i32 s1, s0, 31
	s_lshr_b32 s1, s1, 26
	s_add_i32 s1, s0, s1
	s_ashr_i32 s26, s1, 6
	s_lshl_b32 s26, s26, 3
	s_sub_i32 s27, s41, s26
	s_min_i32 s27, s27, 8
	s_abs_i32 s27, s27
	v_cvt_f32_u32_e32 v4, s27
	s_sub_i32 s28, 0, s27
	s_andn2_b32 s1, s1, 63
	s_sub_i32 s0, s0, s1
	v_rcp_iflag_f32_e32 v4, v4
	s_ashr_i32 s1, s0, 31
	s_abs_i32 s0, s0
	v_mul_f32_e32 v4, 0x4f7ffffe, v4
	v_cvt_u32_f32_e32 v4, v4
	s_nop 0
	v_readfirstlane_b32 s29, v4
	s_mul_i32 s28, s28, s29
	s_mul_hi_u32 s28, s29, s28
	s_add_i32 s29, s29, s28
	s_mul_hi_u32 s28, s0, s29
	s_mul_i32 s28, s28, s27
	s_sub_i32 s0, s0, s28
	s_sub_i32 s28, s0, s27
	s_cmp_ge_u32 s0, s27
	s_cselect_b32 s0, s28, s0
	s_sub_i32 s28, s0, s27
	s_cmp_ge_u32 s0, s27
	s_cselect_b32 s0, s28, s0
	s_xor_b32 s0, s0, s1
	s_sub_i32 s0, s0, s1
	s_add_i32 s1, s26, s38
	s_add_i32 s1, s1, s0
	v_lshl_add_u32 v4, s1, 8, v2
	v_ashrrev_i32_e32 v5, 31, v4
	v_lshl_add_u64 v[4:5], v[4:5], 2, s[16:17]
	global_load_dword v4, v[4:5], off
	s_waitcnt vmcnt(0) lgkmcnt(0)
	v_lshlrev_b32_e32 v4, 10, v4
	ds_write_b32 v3, v4 offset:13312
.LBB0_667:
	s_or_b64 exec, exec, s[24:25]
	v_readlane_b32 s0, v253, 24
	v_mov_b64_e32 v[4:5], s[22:23]
	v_readlane_b32 s1, v253, 25
	s_nop 1
	v_cmp_ge_i64_e32 vcc, s[0:1], v[4:5]
	s_cbranch_vccnz .LBB0_673
	s_and_saveexec_b64 s[24:25], s[10:11]
	s_cbranch_execz .LBB0_670
	v_readlane_b32 s0, v253, 23
	s_or_b32 s0, s41, s0
	v_readlane_b32 s1, v253, 22
	s_mul_i32 s0, s0, s1
	v_readlane_b32 s1, v253, 21
	s_add_i32 s0, s0, s1
	s_ashr_i32 s1, s0, 31
	s_lshr_b32 s1, s1, 26
	s_add_i32 s1, s0, s1
	s_ashr_i32 s10, s1, 6
	s_lshl_b32 s10, s10, 3
	s_sub_i32 s11, s41, s10
	s_min_i32 s11, s11, 8
	s_abs_i32 s11, s11
	v_cvt_f32_u32_e32 v4, s11
	s_sub_i32 s26, 0, s11
	s_andn2_b32 s1, s1, 63
	s_sub_i32 s0, s0, s1
	v_rcp_iflag_f32_e32 v4, v4
	s_ashr_i32 s1, s0, 31
	s_abs_i32 s0, s0
	v_mul_f32_e32 v4, 0x4f7ffffe, v4
	v_cvt_u32_f32_e32 v4, v4
	s_nop 0
	v_readfirstlane_b32 s27, v4
	s_mul_i32 s26, s26, s27
	s_mul_hi_u32 s26, s27, s26
	s_add_i32 s27, s27, s26
	s_mul_hi_u32 s26, s0, s27
	s_mul_i32 s26, s26, s11
	s_sub_i32 s0, s0, s26
	s_sub_i32 s26, s0, s11
	s_cmp_ge_u32 s0, s11
	s_cselect_b32 s0, s26, s0
	s_sub_i32 s26, s0, s11
	s_cmp_ge_u32 s0, s11
	s_cselect_b32 s0, s26, s0
	s_xor_b32 s0, s0, s1
	s_sub_i32 s0, s0, s1
	s_add_i32 s1, s10, s38
	s_add_i32 s1, s1, s0
	v_lshl_add_u32 v4, s1, 8, v2
	v_ashrrev_i32_e32 v5, 31, v4
	v_lshl_add_u64 v[4:5], v[4:5], 2, s[16:17]
	global_load_dword v4, v[4:5], off
	s_waitcnt vmcnt(0) lgkmcnt(0)
	v_lshlrev_b32_e32 v4, 10, v4
	ds_write_b32 v3, v4 offset:14336
.LBB0_670:
	s_or_b64 exec, exec, s[24:25]
	v_readlane_b32 s0, v253, 27
	v_mov_b64_e32 v[4:5], s[22:23]
	v_readlane_b32 s1, v253, 28
	s_nop 1
	v_cmp_lt_i64_e32 vcc, s[0:1], v[4:5]
	s_xor_b64 s[0:1], s[8:9], -1
	s_and_b64 s[0:1], vcc, s[0:1]
	s_and_saveexec_b64 s[8:9], s[0:1]
	s_cbranch_execz .LBB0_672
	v_readlane_b32 s0, v253, 30
	s_or_b32 s0, s41, s0
	v_readlane_b32 s1, v253, 29
	s_mul_i32 s0, s0, s1
	v_readlane_b32 s1, v253, 26
	s_add_i32 s0, s0, s1
	s_ashr_i32 s1, s0, 31
	s_lshr_b32 s1, s1, 26
	s_add_i32 s1, s0, s1
	s_ashr_i32 s10, s1, 6
	s_lshl_b32 s10, s10, 3
	s_sub_i32 s11, s41, s10
	s_min_i32 s11, s11, 8
	s_abs_i32 s11, s11
	v_cvt_f32_u32_e32 v4, s11
	s_sub_i32 s24, 0, s11
	s_andn2_b32 s1, s1, 63
	s_sub_i32 s0, s0, s1
	v_rcp_iflag_f32_e32 v4, v4
	s_ashr_i32 s1, s0, 31
	s_abs_i32 s0, s0
	v_mul_f32_e32 v4, 0x4f7ffffe, v4
	v_cvt_u32_f32_e32 v4, v4
	s_nop 0
	v_readfirstlane_b32 s25, v4
	s_mul_i32 s24, s24, s25
	s_mul_hi_u32 s24, s25, s24
	s_add_i32 s25, s25, s24
	s_mul_hi_u32 s24, s0, s25
	s_mul_i32 s24, s24, s11
	s_sub_i32 s0, s0, s24
	s_sub_i32 s24, s0, s11
	s_cmp_ge_u32 s0, s11
	s_cselect_b32 s0, s24, s0
	s_sub_i32 s24, s0, s11
	s_cmp_ge_u32 s0, s11
	s_cselect_b32 s0, s24, s0
	s_xor_b32 s0, s0, s1
	s_sub_i32 s0, s0, s1
	s_add_i32 s1, s10, s38
	s_add_i32 s1, s1, s0
	v_lshl_add_u32 v4, s1, 8, v2
	v_ashrrev_i32_e32 v5, 31, v4
	v_lshl_add_u64 v[4:5], v[4:5], 2, s[16:17]
	global_load_dword v4, v[4:5], off
	s_waitcnt vmcnt(0) lgkmcnt(0)
	v_lshlrev_b32_e32 v4, 10, v4
	ds_write_b32 v3, v4 offset:15360

.LBB0_688:
	s_add_u32 s10, s34, 0x100
	s_addc_u32 s11, s35, 0
	s_add_u32 s30, s29, s34
	s_addc_u32 s31, s55, s35
	s_cmpk_eq_i32 s34, 0x300
	s_cselect_b64 vcc, -1, 0
	s_and_b64 s[0:1], vcc, exec
	s_cselect_b32 s1, 0, s10
	s_cselect_b32 s0, 0, s11
	s_cselect_b32 s30, s27, s30
	s_cselect_b32 s31, s25, s31
	s_add_u32 s36, s14, s1
	s_addc_u32 s37, s15, s0
	s_add_i32 s1, 0, 0x10000
	v_add_u32_e32 v14, s1, v197
	ds_read_b128 v[2:5], v14
	ds_read_b128 v[6:9], v14 offset:1024
	ds_read_b128 v[10:13], v14 offset:2048
	ds_read_b128 v[14:17], v14 offset:3072
	v_cndmask_b32_e32 v162, v168, v171, vcc
	v_cndmask_b32_e32 v184, v170, v198, vcc
	v_cndmask_b32_e32 v175, v172, v199, vcc
	v_cndmask_b32_e32 v173, v174, v200, vcc
	v_lshl_add_u64 v[18:19], v[178:179], 0, s[34:35]
	s_add_i32 m0, s45, 0xc000
	ds_read_b128 v[202:205], v169
	ds_read_b128 v[206:209], v169 offset:1024
	ds_read_b128 v[210:213], v169 offset:2048
	ds_read_b128 v[214:217], v169 offset:3072
	ds_read_b128 v[218:221], v169 offset:4096
	ds_read_b128 v[222:225], v169 offset:5120
	ds_read_b128 v[226:229], v169 offset:6144
	ds_read_b128 v[230:233], v169 offset:7168
	global_load_lds_dwordx4 v[18:19], off
	v_lshl_add_u64 v[18:19], v[176:177], 0, s[34:35]
	s_add_i32 m0, s45, 0xe000
	s_nop 0
	global_load_lds_dwordx4 v[18:19], off
	s_waitcnt lgkmcnt(8)
	s_waitcnt vmcnt(10)
	s_barrier
	s_waitcnt lgkmcnt(0)
	s_waitcnt lgkmcnt(0)
	v_mfma_scale_f32_16x16x128_f8f6f4 v[158:161], v[2:9], v[202:209], v[158:161], v188, v188 op_sel_hi:[0,0,0]
	v_mfma_scale_f32_16x16x128_f8f6f4 v[150:153], v[10:17], v[202:209], v[150:153], v188, v188 op_sel_hi:[0,0,0]
	v_mfma_scale_f32_16x16x128_f8f6f4 v[142:145], v[2:9], v[210:217], v[142:145], v188, v188 op_sel_hi:[0,0,0]
	v_mfma_scale_f32_16x16x128_f8f6f4 v[134:137], v[10:17], v[210:217], v[134:137], v188, v188 op_sel_hi:[0,0,0]
	v_mfma_scale_f32_16x16x128_f8f6f4 v[126:129], v[2:9], v[218:225], v[126:129], v188, v188 op_sel_hi:[0,0,0]
	v_mfma_scale_f32_16x16x128_f8f6f4 v[118:121], v[10:17], v[218:225], v[118:121], v188, v188 op_sel_hi:[0,0,0]
	v_mfma_scale_f32_16x16x128_f8f6f4 v[110:113], v[2:9], v[226:233], v[110:113], v188, v188 op_sel_hi:[0,0,0]
	v_mfma_scale_f32_16x16x128_f8f6f4 v[102:105], v[10:17], v[226:233], v[102:105], v188, v188 op_sel_hi:[0,0,0]
	s_barrier
	s_add_i32 s0, 0, 0x14000
	s_add_i32 s1, s1, s43
	v_add_u32_e32 v30, s0, v197
	v_lshl_add_u64 v[180:181], s[30:31], 0, v[164:165]
	s_mov_b32 m0, s1
	ds_read_b128 v[18:21], v30
	ds_read_b128 v[22:25], v30 offset:1024
	ds_read_b128 v[26:29], v30 offset:2048
	ds_read_b128 v[30:33], v30 offset:3072
	global_load_lds_dwordx4 v[180:181], off
	v_lshl_add_u64 v[182:183], s[30:31], 0, v[166:167]
	s_add_i32 m0, s1, 0x2000
	s_nop 0
	global_load_lds_dwordx4 v[182:183], off
	s_waitcnt vmcnt(10)
	s_barrier
	s_waitcnt lgkmcnt(0)
	s_waitcnt lgkmcnt(0)
	v_mfma_scale_f32_16x16x128_f8f6f4 v[154:157], v[18:25], v[202:209], v[154:157], v188, v188 op_sel_hi:[0,0,0]
	v_mfma_scale_f32_16x16x128_f8f6f4 v[146:149], v[26:33], v[202:209], v[146:149], v188, v188 op_sel_hi:[0,0,0]
	v_mfma_scale_f32_16x16x128_f8f6f4 v[138:141], v[18:25], v[210:217], v[138:141], v188, v188 op_sel_hi:[0,0,0]
	v_mfma_scale_f32_16x16x128_f8f6f4 v[130:133], v[26:33], v[210:217], v[130:133], v188, v188 op_sel_hi:[0,0,0]
	v_mfma_scale_f32_16x16x128_f8f6f4 v[122:125], v[18:25], v[218:225], v[122:125], v188, v188 op_sel_hi:[0,0,0]
	v_mfma_scale_f32_16x16x128_f8f6f4 v[114:117], v[26:33], v[218:225], v[114:117], v188, v188 op_sel_hi:[0,0,0]
	v_mfma_scale_f32_16x16x128_f8f6f4 v[106:109], v[18:25], v[226:233], v[106:109], v188, v188 op_sel_hi:[0,0,0]
	v_mfma_scale_f32_16x16x128_f8f6f4 v[98:101], v[26:33], v[226:233], v[98:101], v188, v188 op_sel_hi:[0,0,0]
	s_mov_b32 m0, s45
	s_barrier
	ds_read_b128 v[202:205], v169 offset:16384
	ds_read_b128 v[206:209], v169 offset:17408
	ds_read_b128 v[210:213], v169 offset:18432
	ds_read_b128 v[214:217], v169 offset:19456
	ds_read_b128 v[218:221], v169 offset:20480
	ds_read_b128 v[222:225], v169 offset:21504
	ds_read_b128 v[226:229], v169 offset:22528
	ds_read_b128 v[230:233], v169 offset:23552
	global_load_lds_dwordx4 v162, s[36:37]
	s_mov_b32 m0, s46
	v_mov_b32_e32 v185, v163
	global_load_lds_dwordx4 v184, s[36:37]
	s_waitcnt vmcnt(10)
	s_barrier
	s_waitcnt lgkmcnt(0)
	v_lshl_add_u64 v[186:187], s[36:37], 0, v[162:163]
	v_lshl_add_u64 v[184:185], s[36:37], 0, v[184:185]
	s_waitcnt lgkmcnt(0)
	v_mfma_scale_f32_16x16x128_f8f6f4 v[94:97], v[2:9], v[202:209], v[94:97], v188, v188 op_sel_hi:[0,0,0]
	v_mfma_scale_f32_16x16x128_f8f6f4 v[86:89], v[10:17], v[202:209], v[86:89], v188, v188 op_sel_hi:[0,0,0]
	v_mfma_scale_f32_16x16x128_f8f6f4 v[78:81], v[2:9], v[210:217], v[78:81], v188, v188 op_sel_hi:[0,0,0]
	v_mfma_scale_f32_16x16x128_f8f6f4 v[70:73], v[10:17], v[210:217], v[70:73], v188, v188 op_sel_hi:[0,0,0]
	v_mfma_scale_f32_16x16x128_f8f6f4 v[62:65], v[2:9], v[218:225], v[62:65], v188, v188 op_sel_hi:[0,0,0]
	v_mfma_scale_f32_16x16x128_f8f6f4 v[54:57], v[10:17], v[218:225], v[54:57], v188, v188 op_sel_hi:[0,0,0]
	v_mfma_scale_f32_16x16x128_f8f6f4 v[46:49], v[2:9], v[226:233], v[46:49], v188, v188 op_sel_hi:[0,0,0]
	v_mfma_scale_f32_16x16x128_f8f6f4 v[38:41], v[10:17], v[226:233], v[38:41], v188, v188 op_sel_hi:[0,0,0]
	s_barrier
	s_add_u32 s34, s30, 0x20000
	s_addc_u32 s35, s31, 0
	s_add_i32 s0, s0, s43
	v_lshl_add_u64 v[2:3], s[34:35], 0, v[164:165]
	s_mov_b32 m0, s0
	s_nop 0
	global_load_lds_dwordx4 v[2:3], off
	v_lshl_add_u64 v[2:3], s[34:35], 0, v[166:167]
	s_add_i32 m0, s0, 0x2000
	s_nop 0
	global_load_lds_dwordx4 v[2:3], off
	s_waitcnt vmcnt(10)
	s_barrier
	v_mfma_scale_f32_16x16x128_f8f6f4 v[90:93], v[18:25], v[202:209], v[90:93], v188, v188 op_sel_hi:[0,0,0]
	v_mfma_scale_f32_16x16x128_f8f6f4 v[82:85], v[26:33], v[202:209], v[82:85], v188, v188 op_sel_hi:[0,0,0]
	v_mfma_scale_f32_16x16x128_f8f6f4 v[74:77], v[18:25], v[210:217], v[74:77], v188, v188 op_sel_hi:[0,0,0]
	v_mfma_scale_f32_16x16x128_f8f6f4 v[66:69], v[26:33], v[210:217], v[66:69], v188, v188 op_sel_hi:[0,0,0]
	v_mfma_scale_f32_16x16x128_f8f6f4 v[58:61], v[18:25], v[218:225], v[58:61], v188, v188 op_sel_hi:[0,0,0]
	v_mfma_scale_f32_16x16x128_f8f6f4 v[50:53], v[26:33], v[218:225], v[50:53], v188, v188 op_sel_hi:[0,0,0]
	v_mfma_scale_f32_16x16x128_f8f6f4 v[42:45], v[18:25], v[226:233], v[42:45], v188, v188 op_sel_hi:[0,0,0]
	v_mfma_scale_f32_16x16x128_f8f6f4 v[34:37], v[26:33], v[226:233], v[34:37], v188, v188 op_sel_hi:[0,0,0]
	s_add_i32 s0, 0, 0x18000
	v_add_u32_e32 v14, s0, v197
	s_barrier
	ds_read_b128 v[2:5], v14
	ds_read_b128 v[6:9], v14 offset:1024
	ds_read_b128 v[10:13], v14 offset:2048
	ds_read_b128 v[14:17], v14 offset:3072
	s_mov_b32 m0, s47
	ds_read_b128 v[18:21], v169 offset:32768
	ds_read_b128 v[22:25], v169 offset:33792
	ds_read_b128 v[26:29], v169 offset:34816
	ds_read_b128 v[30:33], v169 offset:35840
	ds_read_b128 v[202:205], v169 offset:36864
	ds_read_b128 v[206:209], v169 offset:37888
	ds_read_b128 v[210:213], v169 offset:38912
	ds_read_b128 v[214:217], v169 offset:39936
	global_load_lds_dwordx4 v175, s[36:37]
	s_mov_b32 m0, s48
	s_nop 0
	global_load_lds_dwordx4 v173, s[36:37]
	s_waitcnt lgkmcnt(8)
	s_waitcnt vmcnt(10)
	s_barrier
	s_waitcnt lgkmcnt(0)
	s_waitcnt lgkmcnt(0)
	v_mfma_scale_f32_16x16x128_f8f6f4 v[158:161], v[2:9], v[18:25], v[158:161], v188, v188 op_sel_hi:[0,0,0]
	v_mfma_scale_f32_16x16x128_f8f6f4 v[150:153], v[10:17], v[18:25], v[150:153], v188, v188 op_sel_hi:[0,0,0]
	v_mfma_scale_f32_16x16x128_f8f6f4 v[142:145], v[2:9], v[26:33], v[142:145], v188, v188 op_sel_hi:[0,0,0]
	v_mfma_scale_f32_16x16x128_f8f6f4 v[134:137], v[10:17], v[26:33], v[134:137], v188, v188 op_sel_hi:[0,0,0]
	v_mfma_scale_f32_16x16x128_f8f6f4 v[126:129], v[2:9], v[202:209], v[126:129], v188, v188 op_sel_hi:[0,0,0]
	v_mfma_scale_f32_16x16x128_f8f6f4 v[118:121], v[10:17], v[202:209], v[118:121], v188, v188 op_sel_hi:[0,0,0]
	v_mfma_scale_f32_16x16x128_f8f6f4 v[110:113], v[2:9], v[210:217], v[110:113], v188, v188 op_sel_hi:[0,0,0]
	v_mfma_scale_f32_16x16x128_f8f6f4 v[102:105], v[10:17], v[210:217], v[102:105], v188, v188 op_sel_hi:[0,0,0]
	s_barrier
	s_add_i32 s34, 0, 0x1c000
	s_add_i32 s0, s0, s43
	v_add_u32_e32 v162, s34, v197
	v_lshl_add_u64 v[180:181], v[180:181], 0, s[20:21]
	s_mov_b32 m0, s0
	ds_read_b128 v[218:221], v162
	ds_read_b128 v[222:225], v162 offset:1024
	ds_read_b128 v[226:229], v162 offset:2048
	ds_read_b128 v[230:233], v162 offset:3072
	global_load_lds_dwordx4 v[180:181], off
	v_lshl_add_u64 v[180:181], v[182:183], 0, s[20:21]
	s_add_i32 m0, s0, 0x2000
	s_nop 0
	global_load_lds_dwordx4 v[180:181], off
	s_waitcnt vmcnt(10)
	s_barrier
	s_waitcnt lgkmcnt(0)
	s_waitcnt lgkmcnt(0)
	v_mfma_scale_f32_16x16x128_f8f6f4 v[154:157], v[218:225], v[18:25], v[154:157], v188, v188 op_sel_hi:[0,0,0]
	v_mfma_scale_f32_16x16x128_f8f6f4 v[146:149], v[226:233], v[18:25], v[146:149], v188, v188 op_sel_hi:[0,0,0]
	v_mfma_scale_f32_16x16x128_f8f6f4 v[138:141], v[218:225], v[26:33], v[138:141], v188, v188 op_sel_hi:[0,0,0]
	v_mfma_scale_f32_16x16x128_f8f6f4 v[130:133], v[226:233], v[26:33], v[130:133], v188, v188 op_sel_hi:[0,0,0]
	v_mfma_scale_f32_16x16x128_f8f6f4 v[122:125], v[218:225], v[202:209], v[122:125], v188, v188 op_sel_hi:[0,0,0]
	v_mfma_scale_f32_16x16x128_f8f6f4 v[114:117], v[226:233], v[202:209], v[114:117], v188, v188 op_sel_hi:[0,0,0]
	v_mfma_scale_f32_16x16x128_f8f6f4 v[106:109], v[218:225], v[210:217], v[106:109], v188, v188 op_sel_hi:[0,0,0]
	v_mfma_scale_f32_16x16x128_f8f6f4 v[98:101], v[226:233], v[210:217], v[98:101], v188, v188 op_sel_hi:[0,0,0]
	s_mov_b32 m0, s51
	v_lshl_add_u64 v[180:181], v[186:187], 0, s[20:21]
	s_barrier
	ds_read_b128 v[18:21], v169 offset:49152
	ds_read_b128 v[22:25], v169 offset:50176
	ds_read_b128 v[26:29], v169 offset:51200
	ds_read_b128 v[30:33], v169 offset:52224
	ds_read_b128 v[202:205], v169 offset:53248
	ds_read_b128 v[206:209], v169 offset:54272
	ds_read_b128 v[210:213], v169 offset:55296
	ds_read_b128 v[214:217], v169 offset:56320
	global_load_lds_dwordx4 v[180:181], off
	v_lshl_add_u64 v[180:181], v[184:185], 0, s[20:21]
	s_mov_b32 m0, s52
	s_nop 0
	global_load_lds_dwordx4 v[180:181], off
	s_waitcnt vmcnt(10)
	s_barrier
	s_waitcnt lgkmcnt(0)
	s_waitcnt lgkmcnt(0)
	v_mfma_scale_f32_16x16x128_f8f6f4 v[94:97], v[2:9], v[18:25], v[94:97], v188, v188 op_sel_hi:[0,0,0]
	v_mfma_scale_f32_16x16x128_f8f6f4 v[86:89], v[10:17], v[18:25], v[86:89], v188, v188 op_sel_hi:[0,0,0]
	v_mfma_scale_f32_16x16x128_f8f6f4 v[78:81], v[2:9], v[26:33], v[78:81], v188, v188 op_sel_hi:[0,0,0]
	v_mfma_scale_f32_16x16x128_f8f6f4 v[70:73], v[10:17], v[26:33], v[70:73], v188, v188 op_sel_hi:[0,0,0]
	v_mfma_scale_f32_16x16x128_f8f6f4 v[62:65], v[2:9], v[202:209], v[62:65], v188, v188 op_sel_hi:[0,0,0]
	v_mfma_scale_f32_16x16x128_f8f6f4 v[54:57], v[10:17], v[202:209], v[54:57], v188, v188 op_sel_hi:[0,0,0]
	v_mfma_scale_f32_16x16x128_f8f6f4 v[46:49], v[2:9], v[210:217], v[46:49], v188, v188 op_sel_hi:[0,0,0]
	v_mfma_scale_f32_16x16x128_f8f6f4 v[38:41], v[10:17], v[210:217], v[38:41], v188, v188 op_sel_hi:[0,0,0]
	s_barrier
	s_add_u32 s0, s30, 0x20080
	s_addc_u32 s1, s31, 0
	s_add_i32 s30, s34, s43
	v_lshl_add_u64 v[2:3], s[0:1], 0, v[164:165]
	s_mov_b32 m0, s30
	s_nop 0
	global_load_lds_dwordx4 v[2:3], off
	v_lshl_add_u64 v[2:3], s[0:1], 0, v[166:167]
	s_add_i32 m0, s30, 0x2000
	s_nop 0
	global_load_lds_dwordx4 v[2:3], off
	s_waitcnt vmcnt(10)
	s_barrier
	v_mfma_scale_f32_16x16x128_f8f6f4 v[90:93], v[218:225], v[18:25], v[90:93], v188, v188 op_sel_hi:[0,0,0]
	v_mfma_scale_f32_16x16x128_f8f6f4 v[82:85], v[226:233], v[18:25], v[82:85], v188, v188 op_sel_hi:[0,0,0]
	v_mfma_scale_f32_16x16x128_f8f6f4 v[74:77], v[218:225], v[26:33], v[74:77], v188, v188 op_sel_hi:[0,0,0]
	v_mfma_scale_f32_16x16x128_f8f6f4 v[66:69], v[226:233], v[26:33], v[66:69], v188, v188 op_sel_hi:[0,0,0]
	v_mfma_scale_f32_16x16x128_f8f6f4 v[58:61], v[218:225], v[202:209], v[58:61], v188, v188 op_sel_hi:[0,0,0]
	v_mfma_scale_f32_16x16x128_f8f6f4 v[50:53], v[226:233], v[202:209], v[50:53], v188, v188 op_sel_hi:[0,0,0]
	v_mfma_scale_f32_16x16x128_f8f6f4 v[42:45], v[218:225], v[210:217], v[42:45], v188, v188 op_sel_hi:[0,0,0]
	v_mfma_scale_f32_16x16x128_f8f6f4 v[34:37], v[226:233], v[210:217], v[34:37], v188, v188 op_sel_hi:[0,0,0]
	s_add_i32 s56, s56, 2
	s_cmp_gt_u32 s56, 5
	s_mov_b64 s[34:35], s[10:11]
	s_barrier
	s_cbranch_scc0 .LBB0_688
	v_mul_f32_e32 v5, 0x3c800000, v158
	v_mul_f32_e32 v6, 0xbfb8aa3b, v5
	v_exp_f32_e32 v6, v6
	s_ashr_i32 s29, s28, 31
	s_ashr_i32 s27, s26, 31
	s_lshl_b64 s[10:11], s[28:29], 18
	v_add_f32_e32 v6, 1.0, v6
	v_rcp_f32_e32 v6, v6
	s_lshl_b64 s[26:27], s[26:27], 15
	v_mov_b32_e32 v3, v195
	s_add_u32 s0, s6, s10
	v_mul_f32_e32 v5, v5, v6
	v_mul_f32_e32 v6, 0x3c800000, v159
	v_mul_f32_e32 v7, 0xbfb8aa3b, v6
	v_exp_f32_e32 v7, v7
	v_mul_f32_e32 v5, v5, v154
	v_mul_f32_e32 v5, 0x3e000000, v5
	v_med3_f32 v5, v5, s40, v190
	v_add_f32_e32 v7, 1.0, v7
	v_rcp_f32_e32 v7, v7
	s_nop 15
	s_nop 15
	v_mov_b32_e32 v2, v196
	v_mul_f32_e32 v6, v6, v7
	v_mul_f32_e32 v7, 0x3c800000, v160
	v_mul_f32_e32 v8, 0xbfb8aa3b, v7
	v_exp_f32_e32 v8, v8
	v_mul_f32_e32 v6, v6, v155
	v_mul_f32_e32 v6, 0x3e000000, v6
	v_add_u32_e32 v4, s49, v3
	v_add_f32_e32 v8, 1.0, v8
	v_rcp_f32_e32 v8, v8
	s_addc_u32 s1, s7, s11
	s_add_u32 s10, s0, s26
	v_mul_f32_e32 v7, v7, v8
	v_mul_f32_e32 v8, 0x3c800000, v161
	v_mul_f32_e32 v9, 0xbfb8aa3b, v8
	v_exp_f32_e32 v9, v9
	v_mul_f32_e32 v7, v7, v156
	v_mul_f32_e32 v7, 0x3e000000, v7
	v_lshl_add_u32 v2, v2, 3, s50
	v_add_f32_e32 v9, 1.0, v9
	v_rcp_f32_e32 v9, v9
	s_addc_u32 s11, s1, s27
	v_ashrrev_i32_e32 v3, 31, v2
	s_and_b64 vcc, exec, s[8:9]
	v_mul_f32_e32 v8, v8, v9
	v_mul_f32_e32 v9, 0x3c800000, v150
	v_mul_f32_e32 v10, 0xbfb8aa3b, v9
	v_exp_f32_e32 v10, v10
	v_mul_f32_e32 v8, v8, v157
	v_mul_f32_e32 v8, 0x3e000000, v8
	v_mov_b32_e32 v174, v200
	v_add_f32_e32 v10, 1.0, v10
	v_rcp_f32_e32 v10, v10
	v_mov_b32_e32 v172, v199
	v_mov_b32_e32 v170, v198
	v_mov_b32_e32 v168, v171
	v_mul_f32_e32 v9, v9, v10
	v_mul_f32_e32 v10, 0x3c800000, v151
	v_mul_f32_e32 v11, 0xbfb8aa3b, v10
	v_exp_f32_e32 v11, v11
	v_mul_f32_e32 v9, v9, v146
	v_mul_f32_e32 v9, 0x3e000000, v9
	s_mov_b32 s26, s24
	v_add_f32_e32 v11, 1.0, v11
	v_rcp_f32_e32 v11, v11
	s_mov_b32 s28, s54
	s_mov_b64 s[30:31], s[12:13]
	v_mul_f32_e32 v10, v10, v11
	v_mul_f32_e32 v11, 0x3c800000, v152
	v_mul_f32_e32 v12, 0xbfb8aa3b, v11
	v_exp_f32_e32 v12, v12
	v_mul_f32_e32 v10, v10, v147
	v_mul_f32_e32 v10, 0x3e000000, v10
	v_add_f32_e32 v12, 1.0, v12
	v_rcp_f32_e32 v12, v12
	s_nop 0
	v_mul_f32_e32 v11, v11, v12
	v_mul_f32_e32 v12, 0x3c800000, v153
	v_mul_f32_e32 v13, 0xbfb8aa3b, v12
	v_exp_f32_e32 v13, v13
	v_mul_f32_e32 v11, v11, v148
	v_mul_f32_e32 v11, 0x3e000000, v11
	v_add_f32_e32 v13, 1.0, v13
	v_rcp_f32_e32 v13, v13
	s_nop 0
	v_mul_f32_e32 v12, v12, v13
	v_med3_f32 v13, v6, s40, v190
	v_mov_b32_e32 v6, v163
	v_cvt_pk_fp8_f32 v6, v5, v13
	v_med3_f32 v5, v7, s40, v190
	v_med3_f32 v7, v8, s40, v190
	v_med3_f32 v8, v10, s40, v190
	v_cvt_pk_fp8_f32 v6, v5, v7 op_sel:[0,0,1]
	v_med3_f32 v5, v9, s40, v190
	v_mov_b32_e32 v7, v163
	v_cvt_pk_fp8_f32 v7, v5, v8
	v_mul_f32_e32 v12, v12, v149
	v_mul_f32_e32 v12, 0x3e000000, v12
	v_med3_f32 v5, v11, s40, v190
	v_med3_f32 v8, v12, s40, v190
	v_cvt_pk_fp8_f32 v7, v5, v8 op_sel:[0,0,1]
	v_ashrrev_i32_e32 v5, 31, v4
	v_lshlrev_b64 v[8:9], 7, v[4:5]
	v_lshl_add_u64 v[8:9], s[10:11], 0, v[8:9]
	v_lshl_add_u64 v[8:9], v[8:9], 0, v[2:3]
	v_mul_f32_e32 v5, 0x3c800000, v142
	global_store_dwordx2 v[8:9], v[6:7], off
	v_mul_f32_e32 v6, 0xbfb8aa3b, v5
	v_exp_f32_e32 v6, v6
	s_nop 0
	v_add_f32_e32 v6, 1.0, v6
	v_rcp_f32_e32 v6, v6
	s_nop 0
	v_mul_f32_e32 v5, v5, v6
	v_mul_f32_e32 v6, 0x3c800000, v143
	v_mul_f32_e32 v7, 0xbfb8aa3b, v6
	v_exp_f32_e32 v7, v7
	v_mul_f32_e32 v5, v5, v138
	v_mul_f32_e32 v5, 0x3e000000, v5
	v_med3_f32 v5, v5, s40, v190
	v_add_f32_e32 v7, 1.0, v7
	v_rcp_f32_e32 v7, v7
	s_nop 0
	v_mul_f32_e32 v6, v6, v7
	v_mul_f32_e32 v6, v6, v139
	v_mul_f32_e32 v7, 0x3e000000, v6
	v_mul_f32_e32 v6, 0x3c800000, v144
	v_mul_f32_e32 v8, 0xbfb8aa3b, v6
	v_exp_f32_e32 v8, v8
	v_med3_f32 v7, v7, s40, v190
	v_add_f32_e32 v8, 1.0, v8
	v_rcp_f32_e32 v8, v8
	s_nop 0
	v_mul_f32_e32 v6, v6, v8
	v_mul_f32_e32 v6, v6, v140
	v_mul_f32_e32 v9, 0x3e000000, v6
	v_mul_f32_e32 v6, 0x3c800000, v145
	v_mul_f32_e32 v8, 0xbfb8aa3b, v6
	v_exp_f32_e32 v8, v8
	s_nop 0
	v_add_f32_e32 v8, 1.0, v8
	v_rcp_f32_e32 v8, v8
	s_nop 0
	v_mul_f32_e32 v6, v6, v8
	v_mul_f32_e32 v6, v6, v141
	v_mul_f32_e32 v10, 0x3e000000, v6
	v_mul_f32_e32 v6, 0x3c800000, v134
	v_mul_f32_e32 v8, 0xbfb8aa3b, v6
	v_exp_f32_e32 v8, v8
	s_nop 0
	v_add_f32_e32 v8, 1.0, v8
	v_rcp_f32_e32 v8, v8
	s_nop 0
	v_mul_f32_e32 v6, v6, v8
	v_mul_f32_e32 v6, v6, v130
	v_mul_f32_e32 v11, 0x3e000000, v6
	v_mul_f32_e32 v6, 0x3c800000, v135
	v_mul_f32_e32 v8, 0xbfb8aa3b, v6
	v_exp_f32_e32 v8, v8
	s_nop 0
	v_add_f32_e32 v8, 1.0, v8
	v_rcp_f32_e32 v8, v8
	s_nop 0
	v_mul_f32_e32 v6, v6, v8
	v_mul_f32_e32 v6, v6, v131
	v_mul_f32_e32 v12, 0x3e000000, v6
	v_mul_f32_e32 v6, 0x3c800000, v136
	v_mul_f32_e32 v8, 0xbfb8aa3b, v6
	v_exp_f32_e32 v8, v8
	s_nop 0
	v_add_f32_e32 v8, 1.0, v8
	v_rcp_f32_e32 v8, v8
	s_nop 0
	v_mul_f32_e32 v6, v6, v8
	v_mul_f32_e32 v6, v6, v132
	v_mul_f32_e32 v13, 0x3e000000, v6
	v_mul_f32_e32 v6, 0x3c800000, v137
	v_mul_f32_e32 v8, 0xbfb8aa3b, v6
	v_exp_f32_e32 v8, v8
	s_nop 0
	v_add_f32_e32 v8, 1.0, v8
	v_rcp_f32_e32 v8, v8
	s_nop 0
	v_mul_f32_e32 v6, v6, v8
	v_mov_b32_e32 v8, v163
	v_cvt_pk_fp8_f32 v8, v5, v7
	v_med3_f32 v5, v9, s40, v190
	v_med3_f32 v7, v10, s40, v190
	v_mov_b32_e32 v9, v163
	v_cvt_pk_fp8_f32 v8, v5, v7 op_sel:[0,0,1]
	v_med3_f32 v5, v11, s40, v190
	v_med3_f32 v7, v12, s40, v190
	v_cvt_pk_fp8_f32 v9, v5, v7
	v_mul_f32_e32 v6, v6, v133
	v_mul_f32_e32 v14, 0x3e000000, v6
	v_add_u32_e32 v6, 16, v4
	v_med3_f32 v5, v13, s40, v190
	v_med3_f32 v7, v14, s40, v190
	v_cvt_pk_fp8_f32 v9, v5, v7 op_sel:[0,0,1]
	v_ashrrev_i32_e32 v7, 31, v6
	v_lshlrev_b64 v[6:7], 7, v[6:7]
	v_lshl_add_u64 v[6:7], s[10:11], 0, v[6:7]
	v_lshl_add_u64 v[6:7], v[6:7], 0, v[2:3]
	v_mul_f32_e32 v5, 0x3c800000, v126
	global_store_dwordx2 v[6:7], v[8:9], off
	v_mul_f32_e32 v6, 0xbfb8aa3b, v5
	v_exp_f32_e32 v6, v6
	s_nop 0
	v_add_f32_e32 v6, 1.0, v6
	v_rcp_f32_e32 v6, v6
	s_nop 0
	v_mul_f32_e32 v5, v5, v6
	v_mul_f32_e32 v6, 0x3c800000, v127
	v_mul_f32_e32 v7, 0xbfb8aa3b, v6
	v_exp_f32_e32 v7, v7
	v_mul_f32_e32 v5, v5, v122
	v_mul_f32_e32 v5, 0x3e000000, v5
	v_med3_f32 v5, v5, s40, v190
	v_add_f32_e32 v7, 1.0, v7
	v_rcp_f32_e32 v7, v7
	s_nop 0
	v_mul_f32_e32 v6, v6, v7
	v_mul_f32_e32 v6, v6, v123
	v_mul_f32_e32 v7, 0x3e000000, v6
	v_mul_f32_e32 v6, 0x3c800000, v128
	v_mul_f32_e32 v8, 0xbfb8aa3b, v6
	v_exp_f32_e32 v8, v8
	v_med3_f32 v7, v7, s40, v190
	v_add_f32_e32 v8, 1.0, v8
	v_rcp_f32_e32 v8, v8
	s_nop 0
	v_mul_f32_e32 v6, v6, v8
	v_mul_f32_e32 v6, v6, v124
	v_mul_f32_e32 v9, 0x3e000000, v6
	v_mul_f32_e32 v6, 0x3c800000, v129
	v_mul_f32_e32 v8, 0xbfb8aa3b, v6
	v_exp_f32_e32 v8, v8
	s_nop 0
	v_add_f32_e32 v8, 1.0, v8
	v_rcp_f32_e32 v8, v8
	s_nop 0
	v_mul_f32_e32 v6, v6, v8
	v_mul_f32_e32 v6, v6, v125
	v_mul_f32_e32 v10, 0x3e000000, v6
	v_mul_f32_e32 v6, 0x3c800000, v118
	v_mul_f32_e32 v8, 0xbfb8aa3b, v6
	v_exp_f32_e32 v8, v8
	s_nop 0
	v_add_f32_e32 v8, 1.0, v8
	v_rcp_f32_e32 v8, v8
	s_nop 0
	v_mul_f32_e32 v6, v6, v8
	v_mul_f32_e32 v6, v6, v114
	v_mul_f32_e32 v11, 0x3e000000, v6
	v_mul_f32_e32 v6, 0x3c800000, v119
	v_mul_f32_e32 v8, 0xbfb8aa3b, v6
	v_exp_f32_e32 v8, v8
	s_nop 0
	v_add_f32_e32 v8, 1.0, v8
	v_rcp_f32_e32 v8, v8
	s_nop 0
	v_mul_f32_e32 v6, v6, v8
	v_mul_f32_e32 v6, v6, v115
	v_mul_f32_e32 v12, 0x3e000000, v6
	v_mul_f32_e32 v6, 0x3c800000, v120
	v_mul_f32_e32 v8, 0xbfb8aa3b, v6
	v_exp_f32_e32 v8, v8
	s_nop 0
	v_add_f32_e32 v8, 1.0, v8
	v_rcp_f32_e32 v8, v8
	s_nop 0
	v_mul_f32_e32 v6, v6, v8
	v_mul_f32_e32 v6, v6, v116
	v_mul_f32_e32 v13, 0x3e000000, v6
	v_mul_f32_e32 v6, 0x3c800000, v121
	v_mul_f32_e32 v8, 0xbfb8aa3b, v6
	v_exp_f32_e32 v8, v8
	s_nop 0
	v_add_f32_e32 v8, 1.0, v8
	v_rcp_f32_e32 v8, v8
	s_nop 0
	v_mul_f32_e32 v6, v6, v8
	v_mov_b32_e32 v8, v163
	v_cvt_pk_fp8_f32 v8, v5, v7
	v_med3_f32 v5, v9, s40, v190
	v_med3_f32 v7, v10, s40, v190
	v_mov_b32_e32 v9, v163
	v_cvt_pk_fp8_f32 v8, v5, v7 op_sel:[0,0,1]
	v_med3_f32 v5, v11, s40, v190
	v_med3_f32 v7, v12, s40, v190
	v_cvt_pk_fp8_f32 v9, v5, v7
	v_mul_f32_e32 v6, v6, v117
	v_mul_f32_e32 v14, 0x3e000000, v6
	v_add_u32_e32 v6, 32, v4
	v_med3_f32 v5, v13, s40, v190
	v_med3_f32 v7, v14, s40, v190
	v_cvt_pk_fp8_f32 v9, v5, v7 op_sel:[0,0,1]
	v_ashrrev_i32_e32 v7, 31, v6
	v_lshlrev_b64 v[6:7], 7, v[6:7]
	v_lshl_add_u64 v[6:7], s[10:11], 0, v[6:7]
	v_lshl_add_u64 v[6:7], v[6:7], 0, v[2:3]
	v_mul_f32_e32 v5, 0x3c800000, v110
	global_store_dwordx2 v[6:7], v[8:9], off
	v_mul_f32_e32 v6, 0xbfb8aa3b, v5
	v_exp_f32_e32 v6, v6
	s_nop 0
	v_add_f32_e32 v6, 1.0, v6
	v_rcp_f32_e32 v6, v6
	s_nop 0
	v_mul_f32_e32 v5, v5, v6
	v_mul_f32_e32 v6, 0x3c800000, v111
	v_mul_f32_e32 v7, 0xbfb8aa3b, v6
	v_exp_f32_e32 v7, v7
	v_mul_f32_e32 v5, v5, v106
	v_mul_f32_e32 v5, 0x3e000000, v5
	v_med3_f32 v5, v5, s40, v190
	v_add_f32_e32 v7, 1.0, v7
	v_rcp_f32_e32 v7, v7
	s_nop 0
	v_mul_f32_e32 v6, v6, v7
	v_mul_f32_e32 v6, v6, v107
	v_mul_f32_e32 v7, 0x3e000000, v6
	v_mul_f32_e32 v6, 0x3c800000, v112
	v_mul_f32_e32 v8, 0xbfb8aa3b, v6
	v_exp_f32_e32 v8, v8
	v_med3_f32 v7, v7, s40, v190
	v_add_f32_e32 v8, 1.0, v8
	v_rcp_f32_e32 v8, v8
	s_nop 0
	v_mul_f32_e32 v6, v6, v8
	v_mul_f32_e32 v6, v6, v108
	v_mul_f32_e32 v9, 0x3e000000, v6
	v_mul_f32_e32 v6, 0x3c800000, v113
	v_mul_f32_e32 v8, 0xbfb8aa3b, v6
	v_exp_f32_e32 v8, v8
	s_nop 0
	v_add_f32_e32 v8, 1.0, v8
	v_rcp_f32_e32 v8, v8
	s_nop 0
	v_mul_f32_e32 v6, v6, v8
	v_mul_f32_e32 v6, v6, v109
	v_mul_f32_e32 v10, 0x3e000000, v6
	v_mul_f32_e32 v6, 0x3c800000, v102
	v_mul_f32_e32 v8, 0xbfb8aa3b, v6
	v_exp_f32_e32 v8, v8
	s_nop 0
	v_add_f32_e32 v8, 1.0, v8
	v_rcp_f32_e32 v8, v8
	s_nop 0
	v_mul_f32_e32 v6, v6, v8
	v_mul_f32_e32 v6, v6, v98
	v_mul_f32_e32 v11, 0x3e000000, v6
	v_mul_f32_e32 v6, 0x3c800000, v103
	v_mul_f32_e32 v8, 0xbfb8aa3b, v6
	v_exp_f32_e32 v8, v8
	s_nop 0
	v_add_f32_e32 v8, 1.0, v8
	v_rcp_f32_e32 v8, v8
	s_nop 0
	v_mul_f32_e32 v6, v6, v8
	v_mul_f32_e32 v6, v6, v99
	v_mul_f32_e32 v12, 0x3e000000, v6
	v_mul_f32_e32 v6, 0x3c800000, v104
	v_mul_f32_e32 v8, 0xbfb8aa3b, v6
	v_exp_f32_e32 v8, v8
	s_nop 0
	v_add_f32_e32 v8, 1.0, v8
	v_rcp_f32_e32 v8, v8
	s_nop 0
	v_mul_f32_e32 v6, v6, v8
	v_mul_f32_e32 v6, v6, v100
	v_mul_f32_e32 v13, 0x3e000000, v6
	v_mul_f32_e32 v6, 0x3c800000, v105
	v_mul_f32_e32 v8, 0xbfb8aa3b, v6
	v_exp_f32_e32 v8, v8
	s_nop 0
	v_add_f32_e32 v8, 1.0, v8
	v_rcp_f32_e32 v8, v8
	s_nop 0
	v_mul_f32_e32 v6, v6, v8
	v_mov_b32_e32 v8, v163
	v_cvt_pk_fp8_f32 v8, v5, v7
	v_med3_f32 v5, v9, s40, v190
	v_med3_f32 v7, v10, s40, v190
	v_mov_b32_e32 v9, v163
	v_cvt_pk_fp8_f32 v8, v5, v7 op_sel:[0,0,1]
	v_med3_f32 v5, v11, s40, v190
	v_med3_f32 v7, v12, s40, v190
	v_cvt_pk_fp8_f32 v9, v5, v7
	v_mul_f32_e32 v6, v6, v101
	v_mul_f32_e32 v14, 0x3e000000, v6
	v_add_u32_e32 v6, 48, v4
	v_med3_f32 v5, v13, s40, v190
	v_med3_f32 v7, v14, s40, v190
	v_cvt_pk_fp8_f32 v9, v5, v7 op_sel:[0,0,1]
	v_ashrrev_i32_e32 v7, 31, v6
	v_lshlrev_b64 v[6:7], 7, v[6:7]
	v_lshl_add_u64 v[6:7], s[10:11], 0, v[6:7]
	v_lshl_add_u64 v[6:7], v[6:7], 0, v[2:3]
	v_mul_f32_e32 v5, 0x3c800000, v94
	global_store_dwordx2 v[6:7], v[8:9], off
	v_mul_f32_e32 v7, 0xbfb8aa3b, v5
	v_exp_f32_e32 v7, v7
	v_add_u32_e32 v6, 0x80, v4
	v_add_f32_e32 v7, 1.0, v7
	v_rcp_f32_e32 v7, v7
	s_nop 0
	v_mul_f32_e32 v5, v5, v7
	v_mul_f32_e32 v7, 0x3c800000, v95
	v_mul_f32_e32 v8, 0xbfb8aa3b, v7
	v_exp_f32_e32 v8, v8
	v_mul_f32_e32 v5, v5, v90
	v_mul_f32_e32 v5, 0x3e000000, v5
	v_med3_f32 v5, v5, s40, v190
	v_add_f32_e32 v8, 1.0, v8
	v_rcp_f32_e32 v8, v8
	s_nop 0
	v_mul_f32_e32 v7, v7, v8
	v_mul_f32_e32 v8, 0x3c800000, v96
	v_mul_f32_e32 v9, 0xbfb8aa3b, v8
	v_exp_f32_e32 v9, v9
	v_mul_f32_e32 v7, v7, v91
	v_mul_f32_e32 v7, 0x3e000000, v7
	v_med3_f32 v7, v7, s40, v190
	v_add_f32_e32 v9, 1.0, v9
	v_rcp_f32_e32 v9, v9
	s_nop 0
	v_mul_f32_e32 v8, v8, v9
	v_mul_f32_e32 v8, v8, v92
	v_mul_f32_e32 v9, 0x3e000000, v8
	v_mul_f32_e32 v8, 0x3c800000, v97
	v_mul_f32_e32 v10, 0xbfb8aa3b, v8
	v_exp_f32_e32 v10, v10
	s_nop 0
	v_add_f32_e32 v10, 1.0, v10
	v_rcp_f32_e32 v10, v10
	s_nop 0
	v_mul_f32_e32 v8, v8, v10
	v_mul_f32_e32 v8, v8, v93
	v_mul_f32_e32 v10, 0x3e000000, v8
	v_mul_f32_e32 v8, 0x3c800000, v86
	v_mul_f32_e32 v11, 0xbfb8aa3b, v8
	v_exp_f32_e32 v11, v11
	s_nop 0
	v_add_f32_e32 v11, 1.0, v11
	v_rcp_f32_e32 v11, v11
	s_nop 0
	v_mul_f32_e32 v8, v8, v11
	v_mul_f32_e32 v8, v8, v82
	v_mul_f32_e32 v11, 0x3e000000, v8
	v_mul_f32_e32 v8, 0x3c800000, v87
	v_mul_f32_e32 v12, 0xbfb8aa3b, v8
	v_exp_f32_e32 v12, v12
	s_nop 0
	v_add_f32_e32 v12, 1.0, v12
	v_rcp_f32_e32 v12, v12
	s_nop 0
	v_mul_f32_e32 v8, v8, v12
	v_mul_f32_e32 v8, v8, v83
	v_mul_f32_e32 v12, 0x3e000000, v8
	v_mul_f32_e32 v8, 0x3c800000, v88
	v_mul_f32_e32 v13, 0xbfb8aa3b, v8
	v_exp_f32_e32 v13, v13
	s_nop 0
	v_add_f32_e32 v13, 1.0, v13
	v_rcp_f32_e32 v13, v13
	s_nop 0
	v_mul_f32_e32 v8, v8, v13
	v_mul_f32_e32 v8, v8, v84
	v_mul_f32_e32 v13, 0x3e000000, v8
	v_mul_f32_e32 v8, 0x3c800000, v89
	v_mul_f32_e32 v14, 0xbfb8aa3b, v8
	v_exp_f32_e32 v14, v14
	s_nop 0
	v_add_f32_e32 v14, 1.0, v14
	v_rcp_f32_e32 v14, v14
	s_nop 0
	v_mul_f32_e32 v8, v8, v14
	v_mul_f32_e32 v8, v8, v85
	v_mul_f32_e32 v14, 0x3e000000, v8
	v_mov_b32_e32 v8, v163
	v_cvt_pk_fp8_f32 v8, v5, v7
	v_med3_f32 v5, v9, s40, v190
	v_med3_f32 v7, v10, s40, v190
	v_mov_b32_e32 v9, v163
	v_cvt_pk_fp8_f32 v8, v5, v7 op_sel:[0,0,1]
	v_med3_f32 v5, v11, s40, v190
	v_med3_f32 v7, v12, s40, v190
	v_cvt_pk_fp8_f32 v9, v5, v7
	v_med3_f32 v5, v13, s40, v190
	v_med3_f32 v7, v14, s40, v190
	v_cvt_pk_fp8_f32 v9, v5, v7 op_sel:[0,0,1]
	v_ashrrev_i32_e32 v7, 31, v6
	v_lshlrev_b64 v[6:7], 7, v[6:7]
	v_lshl_add_u64 v[6:7], s[10:11], 0, v[6:7]
	v_lshl_add_u64 v[6:7], v[6:7], 0, v[2:3]
	v_mul_f32_e32 v5, 0x3c800000, v78
	global_store_dwordx2 v[6:7], v[8:9], off
	v_mul_f32_e32 v6, 0xbfb8aa3b, v5
	v_exp_f32_e32 v6, v6
	s_nop 0
	v_add_f32_e32 v6, 1.0, v6
	v_rcp_f32_e32 v6, v6
	s_nop 0
	v_mul_f32_e32 v5, v5, v6
	v_mul_f32_e32 v6, 0x3c800000, v79
	v_mul_f32_e32 v7, 0xbfb8aa3b, v6
	v_exp_f32_e32 v7, v7
	v_mul_f32_e32 v5, v5, v74
	v_mul_f32_e32 v5, 0x3e000000, v5
	v_med3_f32 v5, v5, s40, v190
	v_add_f32_e32 v7, 1.0, v7
	v_rcp_f32_e32 v7, v7
	s_nop 0
	v_mul_f32_e32 v6, v6, v7
	v_mul_f32_e32 v6, v6, v75
	v_mul_f32_e32 v7, 0x3e000000, v6
	v_mul_f32_e32 v6, 0x3c800000, v80
	v_mul_f32_e32 v8, 0xbfb8aa3b, v6
	v_exp_f32_e32 v8, v8
	v_med3_f32 v7, v7, s40, v190
	v_add_f32_e32 v8, 1.0, v8
	v_rcp_f32_e32 v8, v8
	s_nop 0
	v_mul_f32_e32 v6, v6, v8
	v_mul_f32_e32 v6, v6, v76
	v_mul_f32_e32 v9, 0x3e000000, v6
	v_mul_f32_e32 v6, 0x3c800000, v81
	v_mul_f32_e32 v8, 0xbfb8aa3b, v6
	v_exp_f32_e32 v8, v8
	s_nop 0
	v_add_f32_e32 v8, 1.0, v8
	v_rcp_f32_e32 v8, v8
	s_nop 0
	v_mul_f32_e32 v6, v6, v8
	v_mul_f32_e32 v6, v6, v77
	v_mul_f32_e32 v10, 0x3e000000, v6
	v_mul_f32_e32 v6, 0x3c800000, v70
	v_mul_f32_e32 v8, 0xbfb8aa3b, v6
	v_exp_f32_e32 v8, v8
	s_nop 0
	v_add_f32_e32 v8, 1.0, v8
	v_rcp_f32_e32 v8, v8
	s_nop 0
	v_mul_f32_e32 v6, v6, v8
	v_mul_f32_e32 v6, v6, v66
	v_mul_f32_e32 v11, 0x3e000000, v6
	v_mul_f32_e32 v6, 0x3c800000, v71
	v_mul_f32_e32 v8, 0xbfb8aa3b, v6
	v_exp_f32_e32 v8, v8
	s_nop 0
	v_add_f32_e32 v8, 1.0, v8
	v_rcp_f32_e32 v8, v8
	s_nop 0
	v_mul_f32_e32 v6, v6, v8
	v_mul_f32_e32 v6, v6, v67
	v_mul_f32_e32 v12, 0x3e000000, v6
	v_mul_f32_e32 v6, 0x3c800000, v72
	v_mul_f32_e32 v8, 0xbfb8aa3b, v6
	v_exp_f32_e32 v8, v8
	s_nop 0
	v_add_f32_e32 v8, 1.0, v8
	v_rcp_f32_e32 v8, v8
	s_nop 0
	v_mul_f32_e32 v6, v6, v8
	v_mul_f32_e32 v6, v6, v68
	v_mul_f32_e32 v13, 0x3e000000, v6
	v_mul_f32_e32 v6, 0x3c800000, v73
	v_mul_f32_e32 v8, 0xbfb8aa3b, v6
	v_exp_f32_e32 v8, v8
	s_nop 0
	v_add_f32_e32 v8, 1.0, v8
	v_rcp_f32_e32 v8, v8
	s_nop 0
	v_mul_f32_e32 v6, v6, v8
	v_mov_b32_e32 v8, v163
	v_cvt_pk_fp8_f32 v8, v5, v7
	v_med3_f32 v5, v9, s40, v190
	v_med3_f32 v7, v10, s40, v190
	v_mov_b32_e32 v9, v163
	v_cvt_pk_fp8_f32 v8, v5, v7 op_sel:[0,0,1]
	v_med3_f32 v5, v11, s40, v190
	v_med3_f32 v7, v12, s40, v190
	v_cvt_pk_fp8_f32 v9, v5, v7
	v_mul_f32_e32 v6, v6, v69
	v_mul_f32_e32 v14, 0x3e000000, v6
	v_add_u32_e32 v6, 0x90, v4
	v_med3_f32 v5, v13, s40, v190
	v_med3_f32 v7, v14, s40, v190
	v_cvt_pk_fp8_f32 v9, v5, v7 op_sel:[0,0,1]
	v_ashrrev_i32_e32 v7, 31, v6
	v_lshlrev_b64 v[6:7], 7, v[6:7]
	v_lshl_add_u64 v[6:7], s[10:11], 0, v[6:7]
	v_lshl_add_u64 v[6:7], v[6:7], 0, v[2:3]
	v_mul_f32_e32 v5, 0x3c800000, v62
	global_store_dwordx2 v[6:7], v[8:9], off
	v_mul_f32_e32 v6, 0xbfb8aa3b, v5
	v_exp_f32_e32 v6, v6
	s_nop 0
	v_add_f32_e32 v6, 1.0, v6
	v_rcp_f32_e32 v6, v6
	s_nop 0
	v_mul_f32_e32 v5, v5, v6
	v_mul_f32_e32 v6, 0x3c800000, v63
	v_mul_f32_e32 v7, 0xbfb8aa3b, v6
	v_exp_f32_e32 v7, v7
	v_mul_f32_e32 v5, v5, v58
	v_mul_f32_e32 v5, 0x3e000000, v5
	v_med3_f32 v5, v5, s40, v190
	v_add_f32_e32 v7, 1.0, v7
	v_rcp_f32_e32 v7, v7
	s_nop 0
	v_mul_f32_e32 v6, v6, v7
	v_mul_f32_e32 v6, v6, v59
	v_mul_f32_e32 v7, 0x3e000000, v6
	v_mul_f32_e32 v6, 0x3c800000, v64
	v_mul_f32_e32 v8, 0xbfb8aa3b, v6
	v_exp_f32_e32 v8, v8
	v_med3_f32 v7, v7, s40, v190
	v_add_f32_e32 v8, 1.0, v8
	v_rcp_f32_e32 v8, v8
	s_nop 0
	v_mul_f32_e32 v6, v6, v8
	v_mul_f32_e32 v6, v6, v60
	v_mul_f32_e32 v9, 0x3e000000, v6
	v_mul_f32_e32 v6, 0x3c800000, v65
	v_mul_f32_e32 v8, 0xbfb8aa3b, v6
	v_exp_f32_e32 v8, v8
	s_nop 0
	v_add_f32_e32 v8, 1.0, v8
	v_rcp_f32_e32 v8, v8
	s_nop 0
	v_mul_f32_e32 v6, v6, v8
	v_mul_f32_e32 v6, v6, v61
	v_mul_f32_e32 v10, 0x3e000000, v6
	v_mul_f32_e32 v6, 0x3c800000, v54
	v_mul_f32_e32 v8, 0xbfb8aa3b, v6
	v_exp_f32_e32 v8, v8
	s_nop 0
	v_add_f32_e32 v8, 1.0, v8
	v_rcp_f32_e32 v8, v8
	s_nop 0
	v_mul_f32_e32 v6, v6, v8
	v_mul_f32_e32 v6, v6, v50
	v_mul_f32_e32 v11, 0x3e000000, v6
	v_mul_f32_e32 v6, 0x3c800000, v55
	v_mul_f32_e32 v8, 0xbfb8aa3b, v6
	v_exp_f32_e32 v8, v8
	s_nop 0
	v_add_f32_e32 v8, 1.0, v8
	v_rcp_f32_e32 v8, v8
	s_nop 0
	v_mul_f32_e32 v6, v6, v8
	v_mul_f32_e32 v6, v6, v51
	v_mul_f32_e32 v12, 0x3e000000, v6
	v_mul_f32_e32 v6, 0x3c800000, v56
	v_mul_f32_e32 v8, 0xbfb8aa3b, v6
	v_exp_f32_e32 v8, v8
	s_nop 0
	v_add_f32_e32 v8, 1.0, v8
	v_rcp_f32_e32 v8, v8
	s_nop 0
	v_mul_f32_e32 v6, v6, v8
	v_mul_f32_e32 v6, v6, v52
	v_mul_f32_e32 v13, 0x3e000000, v6
	v_mul_f32_e32 v6, 0x3c800000, v57
	v_mul_f32_e32 v8, 0xbfb8aa3b, v6
	v_exp_f32_e32 v8, v8
	s_nop 0
	v_add_f32_e32 v8, 1.0, v8
	v_rcp_f32_e32 v8, v8
	s_nop 0
	v_mul_f32_e32 v6, v6, v8
	v_mov_b32_e32 v8, v163
	v_cvt_pk_fp8_f32 v8, v5, v7
	v_med3_f32 v5, v9, s40, v190
	v_med3_f32 v7, v10, s40, v190
	v_mov_b32_e32 v9, v163
	v_cvt_pk_fp8_f32 v8, v5, v7 op_sel:[0,0,1]
	v_med3_f32 v5, v11, s40, v190
	v_med3_f32 v7, v12, s40, v190
	v_cvt_pk_fp8_f32 v9, v5, v7
	v_mul_f32_e32 v6, v6, v53
	v_mul_f32_e32 v14, 0x3e000000, v6
	v_add_u32_e32 v6, 0xa0, v4
	v_med3_f32 v5, v13, s40, v190
	v_med3_f32 v7, v14, s40, v190
	v_cvt_pk_fp8_f32 v9, v5, v7 op_sel:[0,0,1]
	v_ashrrev_i32_e32 v7, 31, v6
	v_lshlrev_b64 v[6:7], 7, v[6:7]
	v_lshl_add_u64 v[6:7], s[10:11], 0, v[6:7]
	v_lshl_add_u64 v[6:7], v[6:7], 0, v[2:3]
	v_mul_f32_e32 v5, 0x3c800000, v46
	global_store_dwordx2 v[6:7], v[8:9], off
	v_mul_f32_e32 v6, 0xbfb8aa3b, v5
	v_exp_f32_e32 v6, v6
	v_add_u32_e32 v4, 0xb0, v4
	v_add_f32_e32 v6, 1.0, v6
	v_rcp_f32_e32 v6, v6
	s_nop 0
	v_mul_f32_e32 v5, v5, v6
	v_mul_f32_e32 v6, 0x3c800000, v47
	v_mul_f32_e32 v7, 0xbfb8aa3b, v6
	v_exp_f32_e32 v7, v7
	v_mul_f32_e32 v5, v5, v42
	v_mul_f32_e32 v5, 0x3e000000, v5
	v_med3_f32 v5, v5, s40, v190
	v_add_f32_e32 v7, 1.0, v7
	v_rcp_f32_e32 v7, v7
	s_nop 0
	v_mul_f32_e32 v6, v6, v7
	v_mul_f32_e32 v7, 0x3c800000, v48
	v_mul_f32_e32 v8, 0xbfb8aa3b, v7
	v_exp_f32_e32 v8, v8
	v_mul_f32_e32 v6, v6, v43
	v_mul_f32_e32 v6, 0x3e000000, v6
	v_add_f32_e32 v8, 1.0, v8
	v_rcp_f32_e32 v8, v8
	s_nop 0
	v_mul_f32_e32 v7, v7, v8
	v_mul_f32_e32 v8, 0x3c800000, v49
	v_mul_f32_e32 v9, 0xbfb8aa3b, v8
	v_exp_f32_e32 v9, v9
	v_mul_f32_e32 v7, v7, v44
	v_mul_f32_e32 v7, 0x3e000000, v7
	v_add_f32_e32 v9, 1.0, v9
	v_rcp_f32_e32 v9, v9
	s_nop 0
	v_mul_f32_e32 v8, v8, v9
	v_mul_f32_e32 v9, 0x3c800000, v38
	v_mul_f32_e32 v10, 0xbfb8aa3b, v9
	v_exp_f32_e32 v10, v10
	v_mul_f32_e32 v8, v8, v45
	v_mul_f32_e32 v8, 0x3e000000, v8
	v_add_f32_e32 v10, 1.0, v10
	v_rcp_f32_e32 v10, v10
	s_nop 0
	v_mul_f32_e32 v9, v9, v10
	v_mul_f32_e32 v10, 0x3c800000, v39
	v_mul_f32_e32 v11, 0xbfb8aa3b, v10
	v_exp_f32_e32 v11, v11
	v_mul_f32_e32 v9, v9, v34
	v_mul_f32_e32 v9, 0x3e000000, v9
	v_add_f32_e32 v11, 1.0, v11
	v_rcp_f32_e32 v11, v11
	s_nop 0
	v_mul_f32_e32 v10, v10, v11
	v_mul_f32_e32 v11, 0x3c800000, v40
	v_mul_f32_e32 v12, 0xbfb8aa3b, v11
	v_exp_f32_e32 v12, v12
	v_mul_f32_e32 v10, v10, v35
	v_mul_f32_e32 v10, 0x3e000000, v10
	v_add_f32_e32 v12, 1.0, v12
	v_rcp_f32_e32 v12, v12
	s_nop 0
	v_mul_f32_e32 v11, v11, v12
	v_mul_f32_e32 v12, 0x3c800000, v41
	v_mul_f32_e32 v13, 0xbfb8aa3b, v12
	v_exp_f32_e32 v13, v13
	v_mul_f32_e32 v11, v11, v36
	v_mul_f32_e32 v11, 0x3e000000, v11
	v_add_f32_e32 v13, 1.0, v13
	v_rcp_f32_e32 v13, v13
	s_nop 0
	v_mul_f32_e32 v12, v12, v13
	v_med3_f32 v13, v6, s40, v190
	v_mov_b32_e32 v6, v163
	v_cvt_pk_fp8_f32 v6, v5, v13
	v_med3_f32 v5, v7, s40, v190
	v_med3_f32 v7, v8, s40, v190
	v_med3_f32 v8, v10, s40, v190
	v_cvt_pk_fp8_f32 v6, v5, v7 op_sel:[0,0,1]
	v_med3_f32 v5, v9, s40, v190
	v_mov_b32_e32 v7, v163
	v_cvt_pk_fp8_f32 v7, v5, v8
	v_mul_f32_e32 v12, v12, v37
	v_mul_f32_e32 v12, 0x3e000000, v12
	v_med3_f32 v5, v11, s40, v190
	v_med3_f32 v8, v12, s40, v190
	v_cvt_pk_fp8_f32 v7, v5, v8 op_sel:[0,0,1]
	v_ashrrev_i32_e32 v5, 31, v4
	v_lshlrev_b64 v[4:5], 7, v[4:5]
	v_lshl_add_u64 v[4:5], s[10:11], 0, v[4:5]
	v_lshl_add_u64 v[2:3], v[4:5], 0, v[2:3]
	global_store_dwordx2 v[2:3], v[6:7], off
	s_cbranch_vccz .LBB0_677
	s_waitcnt vmcnt(0)
	s_cmpk_gt_u32 s42, 0xff
	s_cbranch_scc1 .LBB0_623
	s_barrier
	s_branch .LBB0_623

.LBB0_755:
	ds_read_b128 v[2:5], v169
	ds_read_b128 v[6:9], v169 offset:1024
	ds_read_b128 v[10:13], v169 offset:2048
	ds_read_b128 v[14:17], v169 offset:3072
	s_add_u32 s0, s26, 0x4000
	s_addc_u32 s1, s27, 0
	s_cmp_eq_u32 s53, 4
	s_cselect_b32 s34, s49, s0
	s_cselect_b32 s35, s19, s1
	s_cselect_b32 s28, s50, s51
	s_cselect_b32 s29, s17, s52
	s_add_u32 s30, s34, 0x8000
	s_addc_u32 s31, s35, 0
	v_lshl_add_u64 v[162:163], s[26:27], 0, v[156:157]
	s_add_i32 m0, s25, 0xc000
	ds_read_b128 v[174:177], v170
	ds_read_b128 v[178:181], v170 offset:1024
	ds_read_b128 v[182:185], v170 offset:2048
	ds_read_b128 v[186:189], v170 offset:3072
	ds_read_b128 v[190:193], v170 offset:4096
	ds_read_b128 v[194:197], v170 offset:5120
	ds_read_b128 v[198:201], v170 offset:6144
	ds_read_b128 v[202:205], v170 offset:7168
	global_load_lds_dwordx4 v[162:163], off
	v_lshl_add_u64 v[162:163], s[26:27], 0, v[154:155]
	s_add_i32 m0, s25, 0xe000
	s_nop 0
	global_load_lds_dwordx4 v[162:163], off
	s_waitcnt lgkmcnt(8)
	s_waitcnt vmcnt(10)
	s_barrier
	s_waitcnt lgkmcnt(0)
	s_waitcnt lgkmcnt(0)
	v_mfma_scale_f32_16x16x128_f8f6f4 v[142:145], v[2:9], v[174:181], v[142:145], v171, v171 op_sel_hi:[0,0,0]
	v_mfma_scale_f32_16x16x128_f8f6f4 v[138:141], v[10:17], v[174:181], v[138:141], v171, v171 op_sel_hi:[0,0,0]
	v_mfma_scale_f32_16x16x128_f8f6f4 v[126:129], v[2:9], v[182:189], v[126:129], v171, v171 op_sel_hi:[0,0,0]
	v_mfma_scale_f32_16x16x128_f8f6f4 v[122:125], v[10:17], v[182:189], v[122:125], v171, v171 op_sel_hi:[0,0,0]
	v_mfma_scale_f32_16x16x128_f8f6f4 v[110:113], v[2:9], v[190:197], v[110:113], v171, v171 op_sel_hi:[0,0,0]
	v_mfma_scale_f32_16x16x128_f8f6f4 v[106:109], v[10:17], v[190:197], v[106:109], v171, v171 op_sel_hi:[0,0,0]
	v_mfma_scale_f32_16x16x128_f8f6f4 v[94:97], v[2:9], v[198:205], v[94:97], v171, v171 op_sel_hi:[0,0,0]
	v_mfma_scale_f32_16x16x128_f8f6f4 v[90:93], v[10:17], v[198:205], v[90:93], v171, v171 op_sel_hi:[0,0,0]
	s_barrier
	s_add_i32 s0, s45, s36
	v_lshl_add_u64 v[162:163], s[28:29], 0, v[150:151]
	s_mov_b32 m0, s0
	ds_read_b128 v[206:209], v172
	ds_read_b128 v[210:213], v172 offset:1024
	ds_read_b128 v[214:217], v172 offset:2048
	ds_read_b128 v[218:221], v172 offset:3072
	global_load_lds_dwordx4 v[162:163], off
	v_lshl_add_u64 v[164:165], s[28:29], 0, v[146:147]
	s_add_i32 m0, s0, 0x2000
	s_nop 0
	global_load_lds_dwordx4 v[164:165], off
	s_waitcnt vmcnt(10)
	s_barrier
	s_waitcnt lgkmcnt(0)
	s_waitcnt lgkmcnt(0)
	v_mfma_scale_f32_16x16x128_f8f6f4 v[134:137], v[206:213], v[174:181], v[134:137], v171, v171 op_sel_hi:[0,0,0]
	v_mfma_scale_f32_16x16x128_f8f6f4 v[130:133], v[214:221], v[174:181], v[130:133], v171, v171 op_sel_hi:[0,0,0]
	v_mfma_scale_f32_16x16x128_f8f6f4 v[118:121], v[206:213], v[182:189], v[118:121], v171, v171 op_sel_hi:[0,0,0]
	v_mfma_scale_f32_16x16x128_f8f6f4 v[114:117], v[214:221], v[182:189], v[114:117], v171, v171 op_sel_hi:[0,0,0]
	v_mfma_scale_f32_16x16x128_f8f6f4 v[102:105], v[206:213], v[190:197], v[102:105], v171, v171 op_sel_hi:[0,0,0]
	v_mfma_scale_f32_16x16x128_f8f6f4 v[98:101], v[214:221], v[190:197], v[98:101], v171, v171 op_sel_hi:[0,0,0]
	v_mfma_scale_f32_16x16x128_f8f6f4 v[86:89], v[206:213], v[198:205], v[86:89], v171, v171 op_sel_hi:[0,0,0]
	v_mfma_scale_f32_16x16x128_f8f6f4 v[82:85], v[214:221], v[198:205], v[82:85], v171, v171 op_sel_hi:[0,0,0]
	s_mov_b32 m0, s25
	v_lshl_add_u64 v[222:223], s[34:35], 0, v[152:153]
	s_barrier
	ds_read_b128 v[174:177], v170 offset:16384
	ds_read_b128 v[178:181], v170 offset:17408
	ds_read_b128 v[182:185], v170 offset:18432
	ds_read_b128 v[186:189], v170 offset:19456
	ds_read_b128 v[190:193], v170 offset:20480
	ds_read_b128 v[194:197], v170 offset:21504
	ds_read_b128 v[198:201], v170 offset:22528
	ds_read_b128 v[202:205], v170 offset:23552
	global_load_lds_dwordx4 v[222:223], off
	v_lshl_add_u64 v[222:223], s[34:35], 0, v[148:149]
	s_mov_b32 m0, s37
	s_nop 0
	global_load_lds_dwordx4 v[222:223], off
	s_waitcnt vmcnt(10)
	s_barrier
	s_waitcnt lgkmcnt(0)
	s_waitcnt lgkmcnt(0)
	v_mfma_scale_f32_16x16x128_f8f6f4 v[78:81], v[2:9], v[174:181], v[78:81], v171, v171 op_sel_hi:[0,0,0]
	v_mfma_scale_f32_16x16x128_f8f6f4 v[74:77], v[10:17], v[174:181], v[74:77], v171, v171 op_sel_hi:[0,0,0]
	v_mfma_scale_f32_16x16x128_f8f6f4 v[62:65], v[2:9], v[182:189], v[62:65], v171, v171 op_sel_hi:[0,0,0]
	v_mfma_scale_f32_16x16x128_f8f6f4 v[58:61], v[10:17], v[182:189], v[58:61], v171, v171 op_sel_hi:[0,0,0]
	v_mfma_scale_f32_16x16x128_f8f6f4 v[46:49], v[2:9], v[190:197], v[46:49], v171, v171 op_sel_hi:[0,0,0]
	v_mfma_scale_f32_16x16x128_f8f6f4 v[42:45], v[10:17], v[190:197], v[42:45], v171, v171 op_sel_hi:[0,0,0]
	v_mfma_scale_f32_16x16x128_f8f6f4 v[30:33], v[2:9], v[198:205], v[30:33], v171, v171 op_sel_hi:[0,0,0]
	v_mfma_scale_f32_16x16x128_f8f6f4 v[26:29], v[10:17], v[198:205], v[26:29], v171, v171 op_sel_hi:[0,0,0]
	s_barrier
	s_add_u32 s0, s28, 0x20000
	s_addc_u32 s1, s29, 0
	s_add_i32 s54, s46, s36
	v_lshl_add_u64 v[2:3], s[0:1], 0, v[150:151]
	s_mov_b32 m0, s54
	s_nop 0
	global_load_lds_dwordx4 v[2:3], off
	v_lshl_add_u64 v[2:3], s[0:1], 0, v[146:147]
	s_add_i32 m0, s54, 0x2000
	s_nop 0
	global_load_lds_dwordx4 v[2:3], off
	s_waitcnt vmcnt(10)
	s_barrier
	v_mfma_scale_f32_16x16x128_f8f6f4 v[70:73], v[206:213], v[174:181], v[70:73], v171, v171 op_sel_hi:[0,0,0]
	v_mfma_scale_f32_16x16x128_f8f6f4 v[66:69], v[214:221], v[174:181], v[66:69], v171, v171 op_sel_hi:[0,0,0]
	v_mfma_scale_f32_16x16x128_f8f6f4 v[54:57], v[206:213], v[182:189], v[54:57], v171, v171 op_sel_hi:[0,0,0]
	v_mfma_scale_f32_16x16x128_f8f6f4 v[50:53], v[214:221], v[182:189], v[50:53], v171, v171 op_sel_hi:[0,0,0]
	v_mfma_scale_f32_16x16x128_f8f6f4 v[38:41], v[206:213], v[190:197], v[38:41], v171, v171 op_sel_hi:[0,0,0]
	v_mfma_scale_f32_16x16x128_f8f6f4 v[34:37], v[214:221], v[190:197], v[34:37], v171, v171 op_sel_hi:[0,0,0]
	v_mfma_scale_f32_16x16x128_f8f6f4 v[22:25], v[206:213], v[198:205], v[22:25], v171, v171 op_sel_hi:[0,0,0]
	v_mfma_scale_f32_16x16x128_f8f6f4 v[18:21], v[214:221], v[198:205], v[18:21], v171, v171 op_sel_hi:[0,0,0]
	s_add_i32 s54, 0, 0x18000
	v_add_u32_e32 v14, s54, v168
	s_barrier
	ds_read_b128 v[2:5], v14
	ds_read_b128 v[6:9], v14 offset:1024
	ds_read_b128 v[10:13], v14 offset:2048
	ds_read_b128 v[14:17], v14 offset:3072
	s_add_u32 s0, s34, 0x4000
	s_addc_u32 s1, s35, 0
	s_mov_b32 m0, s38
	v_lshl_add_u64 v[206:207], s[0:1], 0, v[152:153]
	ds_read_b128 v[174:177], v170 offset:32768
	ds_read_b128 v[178:181], v170 offset:33792
	ds_read_b128 v[182:185], v170 offset:34816
	ds_read_b128 v[186:189], v170 offset:35840
	ds_read_b128 v[190:193], v170 offset:36864
	ds_read_b128 v[194:197], v170 offset:37888
	ds_read_b128 v[198:201], v170 offset:38912
	ds_read_b128 v[202:205], v170 offset:39936
	global_load_lds_dwordx4 v[206:207], off
	v_lshl_add_u64 v[206:207], s[0:1], 0, v[148:149]
	s_mov_b32 m0, s39
	s_nop 0
	global_load_lds_dwordx4 v[206:207], off
	s_waitcnt lgkmcnt(8)
	s_waitcnt vmcnt(10)
	s_barrier
	s_waitcnt lgkmcnt(0)
	s_waitcnt lgkmcnt(0)
	v_mfma_scale_f32_16x16x128_f8f6f4 v[142:145], v[2:9], v[174:181], v[142:145], v171, v171 op_sel_hi:[0,0,0]
	v_mfma_scale_f32_16x16x128_f8f6f4 v[138:141], v[10:17], v[174:181], v[138:141], v171, v171 op_sel_hi:[0,0,0]
	v_mfma_scale_f32_16x16x128_f8f6f4 v[126:129], v[2:9], v[182:189], v[126:129], v171, v171 op_sel_hi:[0,0,0]
	v_mfma_scale_f32_16x16x128_f8f6f4 v[122:125], v[10:17], v[182:189], v[122:125], v171, v171 op_sel_hi:[0,0,0]
	v_mfma_scale_f32_16x16x128_f8f6f4 v[110:113], v[2:9], v[190:197], v[110:113], v171, v171 op_sel_hi:[0,0,0]
	v_mfma_scale_f32_16x16x128_f8f6f4 v[106:109], v[10:17], v[190:197], v[106:109], v171, v171 op_sel_hi:[0,0,0]
	v_mfma_scale_f32_16x16x128_f8f6f4 v[94:97], v[2:9], v[198:205], v[94:97], v171, v171 op_sel_hi:[0,0,0]
	v_mfma_scale_f32_16x16x128_f8f6f4 v[90:93], v[10:17], v[198:205], v[90:93], v171, v171 op_sel_hi:[0,0,0]
	s_barrier
	s_add_i32 s34, 0, 0x1c000
	s_add_i32 s0, s54, s36
	v_add_u32_e32 v218, s34, v168
	v_lshl_add_u64 v[162:163], v[162:163], 0, s[12:13]
	s_mov_b32 m0, s0
	ds_read_b128 v[206:209], v218
	ds_read_b128 v[210:213], v218 offset:1024
	ds_read_b128 v[214:217], v218 offset:2048
	ds_read_b128 v[218:221], v218 offset:3072
	global_load_lds_dwordx4 v[162:163], off
	v_lshl_add_u64 v[162:163], v[164:165], 0, s[12:13]
	s_add_i32 m0, s0, 0x2000
	s_nop 0
	global_load_lds_dwordx4 v[162:163], off
	s_waitcnt vmcnt(10)
	s_barrier
	s_waitcnt lgkmcnt(0)
	s_waitcnt lgkmcnt(0)
	v_mfma_scale_f32_16x16x128_f8f6f4 v[134:137], v[206:213], v[174:181], v[134:137], v171, v171 op_sel_hi:[0,0,0]
	v_mfma_scale_f32_16x16x128_f8f6f4 v[130:133], v[214:221], v[174:181], v[130:133], v171, v171 op_sel_hi:[0,0,0]
	v_mfma_scale_f32_16x16x128_f8f6f4 v[118:121], v[206:213], v[182:189], v[118:121], v171, v171 op_sel_hi:[0,0,0]
	v_mfma_scale_f32_16x16x128_f8f6f4 v[114:117], v[214:221], v[182:189], v[114:117], v171, v171 op_sel_hi:[0,0,0]
	v_mfma_scale_f32_16x16x128_f8f6f4 v[102:105], v[206:213], v[190:197], v[102:105], v171, v171 op_sel_hi:[0,0,0]
	v_mfma_scale_f32_16x16x128_f8f6f4 v[98:101], v[214:221], v[190:197], v[98:101], v171, v171 op_sel_hi:[0,0,0]
	v_mfma_scale_f32_16x16x128_f8f6f4 v[86:89], v[206:213], v[198:205], v[86:89], v171, v171 op_sel_hi:[0,0,0]
	v_mfma_scale_f32_16x16x128_f8f6f4 v[82:85], v[214:221], v[198:205], v[82:85], v171, v171 op_sel_hi:[0,0,0]
	s_mov_b32 m0, s43
	v_lshl_add_u64 v[162:163], s[30:31], 0, v[152:153]
	s_barrier
	ds_read_b128 v[174:177], v170 offset:49152
	ds_read_b128 v[178:181], v170 offset:50176
	ds_read_b128 v[182:185], v170 offset:51200
	ds_read_b128 v[186:189], v170 offset:52224
	ds_read_b128 v[190:193], v170 offset:53248
	ds_read_b128 v[194:197], v170 offset:54272
	ds_read_b128 v[198:201], v170 offset:55296
	ds_read_b128 v[202:205], v170 offset:56320
	global_load_lds_dwordx4 v[162:163], off
	v_lshl_add_u64 v[162:163], s[30:31], 0, v[148:149]
	s_mov_b32 m0, s44
	s_nop 0
	global_load_lds_dwordx4 v[162:163], off
	s_waitcnt vmcnt(10)
	s_barrier
	s_waitcnt lgkmcnt(0)
	s_waitcnt lgkmcnt(0)
	v_mfma_scale_f32_16x16x128_f8f6f4 v[78:81], v[2:9], v[174:181], v[78:81], v171, v171 op_sel_hi:[0,0,0]
	v_mfma_scale_f32_16x16x128_f8f6f4 v[74:77], v[10:17], v[174:181], v[74:77], v171, v171 op_sel_hi:[0,0,0]
	v_mfma_scale_f32_16x16x128_f8f6f4 v[62:65], v[2:9], v[182:189], v[62:65], v171, v171 op_sel_hi:[0,0,0]
	v_mfma_scale_f32_16x16x128_f8f6f4 v[58:61], v[10:17], v[182:189], v[58:61], v171, v171 op_sel_hi:[0,0,0]
	v_mfma_scale_f32_16x16x128_f8f6f4 v[46:49], v[2:9], v[190:197], v[46:49], v171, v171 op_sel_hi:[0,0,0]
	v_mfma_scale_f32_16x16x128_f8f6f4 v[42:45], v[10:17], v[190:197], v[42:45], v171, v171 op_sel_hi:[0,0,0]
	v_mfma_scale_f32_16x16x128_f8f6f4 v[30:33], v[2:9], v[198:205], v[30:33], v171, v171 op_sel_hi:[0,0,0]
	v_mfma_scale_f32_16x16x128_f8f6f4 v[26:29], v[10:17], v[198:205], v[26:29], v171, v171 op_sel_hi:[0,0,0]
	s_barrier
	s_add_u32 s0, s28, 0x20080
	s_addc_u32 s1, s29, 0
	s_add_i32 s28, s34, s36
	v_lshl_add_u64 v[2:3], s[0:1], 0, v[150:151]
	s_mov_b32 m0, s28
	s_nop 0
	global_load_lds_dwordx4 v[2:3], off
	v_lshl_add_u64 v[2:3], s[0:1], 0, v[146:147]
	s_add_i32 m0, s28, 0x2000
	s_nop 0
	global_load_lds_dwordx4 v[2:3], off
	s_waitcnt vmcnt(10)
	s_barrier
	v_mfma_scale_f32_16x16x128_f8f6f4 v[70:73], v[206:213], v[174:181], v[70:73], v171, v171 op_sel_hi:[0,0,0]
	v_mfma_scale_f32_16x16x128_f8f6f4 v[66:69], v[214:221], v[174:181], v[66:69], v171, v171 op_sel_hi:[0,0,0]
	v_mfma_scale_f32_16x16x128_f8f6f4 v[54:57], v[206:213], v[182:189], v[54:57], v171, v171 op_sel_hi:[0,0,0]
	v_mfma_scale_f32_16x16x128_f8f6f4 v[50:53], v[214:221], v[182:189], v[50:53], v171, v171 op_sel_hi:[0,0,0]
	v_mfma_scale_f32_16x16x128_f8f6f4 v[38:41], v[206:213], v[190:197], v[38:41], v171, v171 op_sel_hi:[0,0,0]
	v_mfma_scale_f32_16x16x128_f8f6f4 v[34:37], v[214:221], v[190:197], v[34:37], v171, v171 op_sel_hi:[0,0,0]
	v_mfma_scale_f32_16x16x128_f8f6f4 v[22:25], v[206:213], v[198:205], v[22:25], v171, v171 op_sel_hi:[0,0,0]
	v_mfma_scale_f32_16x16x128_f8f6f4 v[18:21], v[214:221], v[198:205], v[18:21], v171, v171 op_sel_hi:[0,0,0]
	s_add_i32 s53, s53, 2
	s_add_u32 s51, s51, 0x100
	s_addc_u32 s52, s52, 0
	s_add_u32 s26, s26, 0x10000
	s_addc_u32 s27, s27, 0
	s_cmp_gt_u32 s53, 5
	s_barrier
	s_cbranch_scc0 .LBB0_755
	v_pk_mul_f32 v[10:11], v[142:143], s[14:15] op_sel_hi:[1,0]
	v_pk_mul_f32 v[8:9], v[144:145], s[14:15] op_sel_hi:[1,0]
	v_med3_f32 v5, v10, s47, v173
	v_med3_f32 v11, v11, s47, v173
	v_mov_b32_e32 v10, 0
	v_cvt_pk_fp8_f32 v10, v5, v11
	v_mov_b32_e32 v3, v166
	v_mov_b32_e32 v2, v167
	s_lshl_b32 s0, s48, 8
	v_pk_mul_f32 v[14:15], v[138:139], s[14:15] op_sel_hi:[1,0]
	v_med3_f32 v5, v8, s47, v173
	v_med3_f32 v8, v9, s47, v173
	s_nop 15
	s_nop 15
	s_or_b32 s0, s0, s42
	v_cvt_pk_fp8_f32 v10, v5, v8 op_sel:[0,0,1]
	v_med3_f32 v5, v14, s47, v173
	v_med3_f32 v8, v15, s47, v173
	v_mov_b32_e32 v11, 0
	v_lshl_add_u32 v2, v2, 3, s0
	s_lshl_b32 s0, s24, 8
	v_cvt_pk_fp8_f32 v11, v5, v8
	s_add_i32 s0, s0, s41
	v_add_u32_e32 v4, s0, v3
	v_pk_mul_f32 v[12:13], v[140:141], s[14:15] op_sel_hi:[1,0]
	v_mov_b32_e32 v6, v4
	v_med3_f32 v5, v12, s47, v173
	v_med3_f32 v8, v13, s47, v173
	v_cvt_pk_fp8_f32 v11, v5, v8 op_sel:[0,0,1]
	v_ashrrev_i32_e32 v7, 31, v6
	v_lshlrev_b64 v[6:7], 10, v[6:7]
	v_ashrrev_i32_e32 v3, 31, v2
	v_lshl_add_u64 v[6:7], s[10:11], 0, v[6:7]
	v_lshl_add_u64 v[6:7], v[6:7], 0, v[2:3]
	global_store_dwordx2 v[6:7], v[10:11], off
	v_pk_mul_f32 v[10:11], v[134:135], s[14:15] op_sel_hi:[1,0]
	v_pk_mul_f32 v[8:9], v[136:137], s[14:15] op_sel_hi:[1,0]
	v_med3_f32 v5, v10, s47, v173
	v_med3_f32 v11, v11, s47, v173
	v_mov_b32_e32 v10, 0
	v_cvt_pk_fp8_f32 v10, v5, v11
	v_pk_mul_f32 v[14:15], v[130:131], s[14:15] op_sel_hi:[1,0]
	v_med3_f32 v5, v8, s47, v173
	v_med3_f32 v8, v9, s47, v173
	v_cvt_pk_fp8_f32 v10, v5, v8 op_sel:[0,0,1]
	v_med3_f32 v5, v14, s47, v173
	v_med3_f32 v8, v15, s47, v173
	v_mov_b32_e32 v11, 0
	v_cvt_pk_fp8_f32 v11, v5, v8
	v_pk_mul_f32 v[12:13], v[132:133], s[14:15] op_sel_hi:[1,0]
	v_pk_mul_f32 v[14:15], v[122:123], s[14:15] op_sel_hi:[1,0]
	v_med3_f32 v5, v12, s47, v173
	v_med3_f32 v8, v13, s47, v173
	v_cvt_pk_fp8_f32 v11, v5, v8 op_sel:[0,0,1]
	v_pk_mul_f32 v[8:9], v[128:129], s[14:15] op_sel_hi:[1,0]
	v_pk_mul_f32 v[12:13], v[124:125], s[14:15] op_sel_hi:[1,0]
	s_and_b64 vcc, exec, s[8:9]
	global_store_dwordx2 v[6:7], v[10:11], off offset:128
	v_pk_mul_f32 v[10:11], v[126:127], s[14:15] op_sel_hi:[1,0]
	v_add_u32_e32 v6, 16, v4
	v_med3_f32 v5, v10, s47, v173
	v_med3_f32 v11, v11, s47, v173
	v_mov_b32_e32 v10, 0
	v_cvt_pk_fp8_f32 v10, v5, v11
	v_med3_f32 v5, v8, s47, v173
	v_med3_f32 v8, v9, s47, v173
	v_mov_b32_e32 v11, 0
	v_cvt_pk_fp8_f32 v10, v5, v8 op_sel:[0,0,1]
	v_med3_f32 v5, v14, s47, v173
	v_med3_f32 v8, v15, s47, v173
	v_cvt_pk_fp8_f32 v11, v5, v8
	v_med3_f32 v5, v12, s47, v173
	v_med3_f32 v8, v13, s47, v173
	v_cvt_pk_fp8_f32 v11, v5, v8 op_sel:[0,0,1]
	v_ashrrev_i32_e32 v7, 31, v6
	v_lshlrev_b64 v[6:7], 10, v[6:7]
	v_lshl_add_u64 v[6:7], s[10:11], 0, v[6:7]
	v_lshl_add_u64 v[6:7], v[6:7], 0, v[2:3]
	global_store_dwordx2 v[6:7], v[10:11], off
	v_pk_mul_f32 v[10:11], v[118:119], s[14:15] op_sel_hi:[1,0]
	v_pk_mul_f32 v[8:9], v[120:121], s[14:15] op_sel_hi:[1,0]
	v_med3_f32 v5, v10, s47, v173
	v_med3_f32 v11, v11, s47, v173
	v_mov_b32_e32 v10, 0
	v_cvt_pk_fp8_f32 v10, v5, v11
	v_pk_mul_f32 v[14:15], v[114:115], s[14:15] op_sel_hi:[1,0]
	v_med3_f32 v5, v8, s47, v173
	v_med3_f32 v8, v9, s47, v173
	v_cvt_pk_fp8_f32 v10, v5, v8 op_sel:[0,0,1]
	v_med3_f32 v5, v14, s47, v173
	v_med3_f32 v8, v15, s47, v173
	v_mov_b32_e32 v11, 0
	v_cvt_pk_fp8_f32 v11, v5, v8
	v_pk_mul_f32 v[12:13], v[116:117], s[14:15] op_sel_hi:[1,0]
	v_pk_mul_f32 v[14:15], v[106:107], s[14:15] op_sel_hi:[1,0]
	v_med3_f32 v5, v12, s47, v173
	v_med3_f32 v8, v13, s47, v173
	v_cvt_pk_fp8_f32 v11, v5, v8 op_sel:[0,0,1]
	v_pk_mul_f32 v[8:9], v[112:113], s[14:15] op_sel_hi:[1,0]
	v_pk_mul_f32 v[12:13], v[108:109], s[14:15] op_sel_hi:[1,0]
	s_mov_b32 s48, s16
	global_store_dwordx2 v[6:7], v[10:11], off offset:128
	v_pk_mul_f32 v[10:11], v[110:111], s[14:15] op_sel_hi:[1,0]
	v_add_u32_e32 v6, 32, v4
	v_med3_f32 v5, v10, s47, v173
	v_med3_f32 v11, v11, s47, v173
	v_mov_b32_e32 v10, 0
	v_cvt_pk_fp8_f32 v10, v5, v11
	v_med3_f32 v5, v8, s47, v173
	v_med3_f32 v8, v9, s47, v173
	v_mov_b32_e32 v11, 0
	v_cvt_pk_fp8_f32 v10, v5, v8 op_sel:[0,0,1]
	v_med3_f32 v5, v14, s47, v173
	v_med3_f32 v8, v15, s47, v173
	v_cvt_pk_fp8_f32 v11, v5, v8
	v_med3_f32 v5, v12, s47, v173
	v_med3_f32 v8, v13, s47, v173
	v_cvt_pk_fp8_f32 v11, v5, v8 op_sel:[0,0,1]
	v_ashrrev_i32_e32 v7, 31, v6
	v_lshlrev_b64 v[6:7], 10, v[6:7]
	v_lshl_add_u64 v[6:7], s[10:11], 0, v[6:7]
	v_lshl_add_u64 v[6:7], v[6:7], 0, v[2:3]
	global_store_dwordx2 v[6:7], v[10:11], off
	v_pk_mul_f32 v[10:11], v[102:103], s[14:15] op_sel_hi:[1,0]
	v_pk_mul_f32 v[8:9], v[104:105], s[14:15] op_sel_hi:[1,0]
	v_med3_f32 v5, v10, s47, v173
	v_med3_f32 v11, v11, s47, v173
	v_mov_b32_e32 v10, 0
	v_cvt_pk_fp8_f32 v10, v5, v11
	v_pk_mul_f32 v[14:15], v[98:99], s[14:15] op_sel_hi:[1,0]
	v_med3_f32 v5, v8, s47, v173
	v_med3_f32 v8, v9, s47, v173
	v_cvt_pk_fp8_f32 v10, v5, v8 op_sel:[0,0,1]
	v_med3_f32 v5, v14, s47, v173
	v_med3_f32 v8, v15, s47, v173
	v_mov_b32_e32 v11, 0
	v_cvt_pk_fp8_f32 v11, v5, v8
	v_pk_mul_f32 v[12:13], v[100:101], s[14:15] op_sel_hi:[1,0]
	v_pk_mul_f32 v[14:15], v[90:91], s[14:15] op_sel_hi:[1,0]
	v_med3_f32 v5, v12, s47, v173
	v_med3_f32 v8, v13, s47, v173
	v_cvt_pk_fp8_f32 v11, v5, v8 op_sel:[0,0,1]
	v_pk_mul_f32 v[8:9], v[96:97], s[14:15] op_sel_hi:[1,0]
	v_pk_mul_f32 v[12:13], v[92:93], s[14:15] op_sel_hi:[1,0]
	s_mov_b32 s24, s18
	global_store_dwordx2 v[6:7], v[10:11], off offset:128
	v_pk_mul_f32 v[10:11], v[94:95], s[14:15] op_sel_hi:[1,0]
	v_add_u32_e32 v6, 48, v4
	v_med3_f32 v5, v10, s47, v173
	v_med3_f32 v11, v11, s47, v173
	v_mov_b32_e32 v10, 0
	v_cvt_pk_fp8_f32 v10, v5, v11
	v_med3_f32 v5, v8, s47, v173
	v_med3_f32 v8, v9, s47, v173
	v_mov_b32_e32 v11, 0
	v_cvt_pk_fp8_f32 v10, v5, v8 op_sel:[0,0,1]
	v_med3_f32 v5, v14, s47, v173
	v_med3_f32 v8, v15, s47, v173
	v_cvt_pk_fp8_f32 v11, v5, v8
	v_med3_f32 v5, v12, s47, v173
	v_med3_f32 v8, v13, s47, v173
	v_cvt_pk_fp8_f32 v11, v5, v8 op_sel:[0,0,1]
	v_ashrrev_i32_e32 v7, 31, v6
	v_lshlrev_b64 v[6:7], 10, v[6:7]
	v_lshl_add_u64 v[6:7], s[10:11], 0, v[6:7]
	v_lshl_add_u64 v[6:7], v[6:7], 0, v[2:3]
	global_store_dwordx2 v[6:7], v[10:11], off
	v_pk_mul_f32 v[10:11], v[86:87], s[14:15] op_sel_hi:[1,0]
	v_pk_mul_f32 v[8:9], v[88:89], s[14:15] op_sel_hi:[1,0]
	v_med3_f32 v5, v10, s47, v173
	v_med3_f32 v11, v11, s47, v173
	v_mov_b32_e32 v10, 0
	v_cvt_pk_fp8_f32 v10, v5, v11
	v_pk_mul_f32 v[14:15], v[82:83], s[14:15] op_sel_hi:[1,0]
	v_med3_f32 v5, v8, s47, v173
	v_med3_f32 v8, v9, s47, v173
	v_cvt_pk_fp8_f32 v10, v5, v8 op_sel:[0,0,1]
	v_med3_f32 v5, v14, s47, v173
	v_med3_f32 v8, v15, s47, v173
	v_mov_b32_e32 v11, 0
	v_cvt_pk_fp8_f32 v11, v5, v8
	v_pk_mul_f32 v[12:13], v[84:85], s[14:15] op_sel_hi:[1,0]
	v_pk_mul_f32 v[14:15], v[74:75], s[14:15] op_sel_hi:[1,0]
	v_med3_f32 v5, v12, s47, v173
	v_med3_f32 v8, v13, s47, v173
	v_cvt_pk_fp8_f32 v11, v5, v8 op_sel:[0,0,1]
	v_pk_mul_f32 v[8:9], v[80:81], s[14:15] op_sel_hi:[1,0]
	v_pk_mul_f32 v[12:13], v[76:77], s[14:15] op_sel_hi:[1,0]
	s_mov_b64 s[26:27], s[22:23]
	global_store_dwordx2 v[6:7], v[10:11], off offset:128
	v_pk_mul_f32 v[10:11], v[78:79], s[14:15] op_sel_hi:[1,0]
	v_add_u32_e32 v6, 0x80, v4
	v_med3_f32 v5, v10, s47, v173
	v_med3_f32 v11, v11, s47, v173
	v_mov_b32_e32 v10, 0
	v_cvt_pk_fp8_f32 v10, v5, v11
	v_med3_f32 v5, v8, s47, v173
	v_med3_f32 v8, v9, s47, v173
	v_mov_b32_e32 v11, 0
	v_cvt_pk_fp8_f32 v10, v5, v8 op_sel:[0,0,1]
	v_med3_f32 v5, v14, s47, v173
	v_med3_f32 v8, v15, s47, v173
	v_cvt_pk_fp8_f32 v11, v5, v8
	v_med3_f32 v5, v12, s47, v173
	v_med3_f32 v8, v13, s47, v173
	v_cvt_pk_fp8_f32 v11, v5, v8 op_sel:[0,0,1]
	v_ashrrev_i32_e32 v7, 31, v6
	v_lshlrev_b64 v[6:7], 10, v[6:7]
	v_lshl_add_u64 v[6:7], s[10:11], 0, v[6:7]
	v_lshl_add_u64 v[6:7], v[6:7], 0, v[2:3]
	global_store_dwordx2 v[6:7], v[10:11], off
	v_pk_mul_f32 v[10:11], v[70:71], s[14:15] op_sel_hi:[1,0]
	v_pk_mul_f32 v[8:9], v[72:73], s[14:15] op_sel_hi:[1,0]
	v_med3_f32 v5, v10, s47, v173
	v_med3_f32 v11, v11, s47, v173
	v_mov_b32_e32 v10, 0
	v_cvt_pk_fp8_f32 v10, v5, v11
	v_pk_mul_f32 v[14:15], v[66:67], s[14:15] op_sel_hi:[1,0]
	v_med3_f32 v5, v8, s47, v173
	v_med3_f32 v8, v9, s47, v173
	v_cvt_pk_fp8_f32 v10, v5, v8 op_sel:[0,0,1]
	v_med3_f32 v5, v14, s47, v173
	v_med3_f32 v8, v15, s47, v173
	v_mov_b32_e32 v11, 0
	v_cvt_pk_fp8_f32 v11, v5, v8
	v_pk_mul_f32 v[12:13], v[68:69], s[14:15] op_sel_hi:[1,0]
	v_pk_mul_f32 v[14:15], v[58:59], s[14:15] op_sel_hi:[1,0]
	v_med3_f32 v5, v12, s47, v173
	v_med3_f32 v8, v13, s47, v173
	v_cvt_pk_fp8_f32 v11, v5, v8 op_sel:[0,0,1]
	v_pk_mul_f32 v[8:9], v[64:65], s[14:15] op_sel_hi:[1,0]
	v_pk_mul_f32 v[12:13], v[60:61], s[14:15] op_sel_hi:[1,0]
	s_mov_b64 s[28:29], s[20:21]
	global_store_dwordx2 v[6:7], v[10:11], off offset:128
	v_pk_mul_f32 v[10:11], v[62:63], s[14:15] op_sel_hi:[1,0]
	v_add_u32_e32 v6, 0x90, v4
	v_med3_f32 v5, v10, s47, v173
	v_med3_f32 v11, v11, s47, v173
	v_mov_b32_e32 v10, 0
	v_cvt_pk_fp8_f32 v10, v5, v11
	v_med3_f32 v5, v8, s47, v173
	v_med3_f32 v8, v9, s47, v173
	v_mov_b32_e32 v11, 0
	v_cvt_pk_fp8_f32 v10, v5, v8 op_sel:[0,0,1]
	v_med3_f32 v5, v14, s47, v173
	v_med3_f32 v8, v15, s47, v173
	v_cvt_pk_fp8_f32 v11, v5, v8
	v_med3_f32 v5, v12, s47, v173
	v_med3_f32 v8, v13, s47, v173
	v_cvt_pk_fp8_f32 v11, v5, v8 op_sel:[0,0,1]
	v_ashrrev_i32_e32 v7, 31, v6
	v_lshlrev_b64 v[6:7], 10, v[6:7]
	v_lshl_add_u64 v[6:7], s[10:11], 0, v[6:7]
	v_lshl_add_u64 v[6:7], v[6:7], 0, v[2:3]
	global_store_dwordx2 v[6:7], v[10:11], off
	v_pk_mul_f32 v[10:11], v[54:55], s[14:15] op_sel_hi:[1,0]
	v_pk_mul_f32 v[8:9], v[56:57], s[14:15] op_sel_hi:[1,0]
	v_med3_f32 v5, v10, s47, v173
	v_med3_f32 v11, v11, s47, v173
	v_mov_b32_e32 v10, 0
	v_cvt_pk_fp8_f32 v10, v5, v11
	v_pk_mul_f32 v[14:15], v[50:51], s[14:15] op_sel_hi:[1,0]
	v_med3_f32 v5, v8, s47, v173
	v_med3_f32 v8, v9, s47, v173
	v_cvt_pk_fp8_f32 v10, v5, v8 op_sel:[0,0,1]
	v_med3_f32 v5, v14, s47, v173
	v_med3_f32 v8, v15, s47, v173
	v_mov_b32_e32 v11, 0
	v_cvt_pk_fp8_f32 v11, v5, v8
	v_pk_mul_f32 v[12:13], v[52:53], s[14:15] op_sel_hi:[1,0]
	v_pk_mul_f32 v[14:15], v[42:43], s[14:15] op_sel_hi:[1,0]
	v_med3_f32 v5, v12, s47, v173
	v_med3_f32 v8, v13, s47, v173
	v_cvt_pk_fp8_f32 v11, v5, v8 op_sel:[0,0,1]
	v_pk_mul_f32 v[8:9], v[48:49], s[14:15] op_sel_hi:[1,0]
	v_pk_mul_f32 v[12:13], v[44:45], s[14:15] op_sel_hi:[1,0]
	global_store_dwordx2 v[6:7], v[10:11], off offset:128
	v_pk_mul_f32 v[10:11], v[46:47], s[14:15] op_sel_hi:[1,0]
	v_add_u32_e32 v6, 0xa0, v4
	v_med3_f32 v5, v10, s47, v173
	v_med3_f32 v11, v11, s47, v173
	v_mov_b32_e32 v10, 0
	v_cvt_pk_fp8_f32 v10, v5, v11
	v_med3_f32 v5, v8, s47, v173
	v_med3_f32 v8, v9, s47, v173
	v_mov_b32_e32 v11, 0
	v_cvt_pk_fp8_f32 v10, v5, v8 op_sel:[0,0,1]
	v_med3_f32 v5, v14, s47, v173
	v_med3_f32 v8, v15, s47, v173
	v_cvt_pk_fp8_f32 v11, v5, v8
	v_med3_f32 v5, v12, s47, v173
	v_med3_f32 v8, v13, s47, v173
	v_cvt_pk_fp8_f32 v11, v5, v8 op_sel:[0,0,1]
	v_ashrrev_i32_e32 v7, 31, v6
	v_lshlrev_b64 v[6:7], 10, v[6:7]
	v_lshl_add_u64 v[6:7], s[10:11], 0, v[6:7]
	v_lshl_add_u64 v[6:7], v[6:7], 0, v[2:3]
	global_store_dwordx2 v[6:7], v[10:11], off
	v_pk_mul_f32 v[10:11], v[38:39], s[14:15] op_sel_hi:[1,0]
	v_pk_mul_f32 v[8:9], v[40:41], s[14:15] op_sel_hi:[1,0]
	v_med3_f32 v5, v10, s47, v173
	v_med3_f32 v11, v11, s47, v173
	v_mov_b32_e32 v10, 0
	v_cvt_pk_fp8_f32 v10, v5, v11
	v_pk_mul_f32 v[14:15], v[34:35], s[14:15] op_sel_hi:[1,0]
	v_med3_f32 v5, v8, s47, v173
	v_med3_f32 v8, v9, s47, v173
	v_cvt_pk_fp8_f32 v10, v5, v8 op_sel:[0,0,1]
	v_med3_f32 v5, v14, s47, v173
	v_med3_f32 v8, v15, s47, v173
	v_mov_b32_e32 v11, 0
	v_cvt_pk_fp8_f32 v11, v5, v8
	v_pk_mul_f32 v[12:13], v[36:37], s[14:15] op_sel_hi:[1,0]
	v_add_u32_e32 v4, 0xb0, v4
	v_med3_f32 v5, v12, s47, v173
	v_med3_f32 v8, v13, s47, v173
	v_cvt_pk_fp8_f32 v11, v5, v8 op_sel:[0,0,1]
	v_pk_mul_f32 v[8:9], v[28:29], s[14:15] op_sel_hi:[1,0]
	global_store_dwordx2 v[6:7], v[10:11], off offset:128
	v_pk_mul_f32 v[6:7], v[30:31], s[14:15] op_sel_hi:[1,0]
	v_pk_mul_f32 v[10:11], v[26:27], s[14:15] op_sel_hi:[1,0]
	v_ashrrev_i32_e32 v5, 31, v4
	v_med3_f32 v12, v6, s47, v173
	v_med3_f32 v7, v7, s47, v173
	v_mov_b32_e32 v6, 0
	v_lshlrev_b64 v[4:5], 10, v[4:5]
	v_cvt_pk_fp8_f32 v6, v12, v7
	v_lshl_add_u64 v[4:5], s[10:11], 0, v[4:5]
	v_lshl_add_u64 v[2:3], v[4:5], 0, v[2:3]
	v_pk_mul_f32 v[4:5], v[32:33], s[14:15] op_sel_hi:[1,0]
	v_mov_b32_e32 v7, 0
	v_med3_f32 v4, v4, s47, v173
	v_med3_f32 v5, v5, s47, v173
	v_cvt_pk_fp8_f32 v6, v4, v5 op_sel:[0,0,1]
	v_med3_f32 v4, v10, s47, v173
	v_med3_f32 v5, v11, s47, v173
	v_cvt_pk_fp8_f32 v7, v4, v5
	v_med3_f32 v4, v8, s47, v173
	v_med3_f32 v5, v9, s47, v173
	v_pk_mul_f32 v[10:11], v[18:19], s[14:15] op_sel_hi:[1,0]
	v_cvt_pk_fp8_f32 v7, v4, v5 op_sel:[0,0,1]
	v_pk_mul_f32 v[4:5], v[24:25], s[14:15] op_sel_hi:[1,0]
	v_pk_mul_f32 v[8:9], v[20:21], s[14:15] op_sel_hi:[1,0]
	v_med3_f32 v4, v4, s47, v173
	global_store_dwordx2 v[2:3], v[6:7], off
	v_pk_mul_f32 v[6:7], v[22:23], s[14:15] op_sel_hi:[1,0]
	v_med3_f32 v5, v5, s47, v173
	v_med3_f32 v12, v6, s47, v173
	v_med3_f32 v7, v7, s47, v173
	v_mov_b32_e32 v6, 0
	v_cvt_pk_fp8_f32 v6, v12, v7
	v_mov_b32_e32 v7, 0
	v_cvt_pk_fp8_f32 v6, v4, v5 op_sel:[0,0,1]
	v_med3_f32 v4, v10, s47, v173
	v_med3_f32 v5, v11, s47, v173
	v_cvt_pk_fp8_f32 v7, v4, v5
	v_med3_f32 v4, v8, s47, v173
	v_med3_f32 v5, v9, s47, v173
	v_cvt_pk_fp8_f32 v7, v4, v5 op_sel:[0,0,1]
	global_store_dwordx2 v[2:3], v[6:7], off offset:128
	s_cbranch_vccz .LBB0_748
	s_waitcnt vmcnt(0)
	s_cmpk_gt_u32 s4, 0xff
	s_cbranch_scc1 .LBB0_759
	s_barrier

.LBB0_813:
	s_or_b64 exec, exec, s[8:9]
	s_waitcnt lgkmcnt(0)
	s_barrier
	s_load_dwordx8 s[12:19], s[84:85], 0xd8
	s_load_dwordx4 s[4:7], s[84:85], 0xf8
	s_load_dwordx2 s[20:21], s[84:85], 0x108
	s_add_i32 s8, s33, s68
	s_ashr_i32 s69, s68, 31
	s_ashr_i32 s9, s8, 31
	s_mov_b32 s0, s8
	s_lshl_b64 s[24:25], s[68:69], 11
	v_writelane_b32 v253, s0, 34
	s_lshl_b64 s[26:27], s[8:9], 11
	v_mov_b32_e32 v39, v0
	s_waitcnt lgkmcnt(0)
	s_mov_b32 s8, s21
	v_writelane_b32 v253, s1, 35
	s_mov_b32 s0, s7
	v_and_b32_e32 v74, 63, v39
	s_add_u32 s22, s20, 0x3e00000
	s_addc_u32 s23, s8, 0
	v_lshlrev_b32_e32 v34, 4, v74
	v_mov_b32_e32 v35, 0
	v_lshl_add_u64 v[2:3], s[18:19], 0, v[34:35]
	s_mov_b64 s[0:1], 0x1000
	v_lshl_add_u64 v[6:7], s[4:5], 0, v[34:35]
	s_add_u32 s18, s20, 0x3900000
	v_lshl_add_u64 v[26:27], v[2:3], 0, s[0:1]
	v_lshl_add_u64 v[30:31], v[6:7], 0, s[0:1]
	s_movk_i32 s0, 0x1000
	s_addc_u32 s19, s8, 0
	v_add_co_u32_e32 v2, vcc, s0, v2
	s_add_u32 s10, s20, 0xa100000
	s_nop 0
	v_addc_co_u32_e32 v3, vcc, 0, v3, vcc
	s_addc_u32 s11, s8, 0
	v_add_co_u32_e32 v6, vcc, s0, v6
	s_add_u32 s0, s10, s24
	v_writelane_b32 v253, s24, 36
	s_addc_u32 s1, s11, s25
	s_add_u32 s4, s10, s26
	v_writelane_b32 v253, s25, 37
	v_lshlrev_b32_e32 v34, 3, v74
	v_addc_co_u32_e32 v7, vcc, 0, v7, vcc
	v_writelane_b32 v253, s26, 38
	s_addc_u32 s5, s11, s27
	v_lshl_add_u64 v[36:37], s[0:1], 0, v[34:35]
	global_load_dwordx4 v[2:5], v[2:3], off nt
	s_nop 0
	global_load_dwordx4 v[6:9], v[6:7], off nt
	s_nop 0
	global_load_dwordx4 v[10:13], v[26:27], off offset:1024
	global_load_dwordx4 v[14:17], v[26:27], off offset:2048
	global_load_dwordx4 v[18:21], v[30:31], off offset:1024
	global_load_dwordx4 v[22:25], v[30:31], off offset:2048
	s_nop 0
	global_load_dwordx4 v[26:29], v[26:27], off offset:3072
	s_nop 0
	global_load_dwordx4 v[30:33], v[30:31], off offset:3072
	v_lshl_add_u64 v[46:47], s[4:5], 0, v[34:35]
	global_load_dwordx2 v[64:65], v[36:37], off
	global_load_dwordx2 v[62:63], v[36:37], off offset:512
	global_load_dwordx2 v[60:61], v[36:37], off offset:1024
	global_load_dwordx2 v[58:59], v[36:37], off offset:1536
	global_load_dwordx2 v[44:45], v[46:47], off
	global_load_dwordx2 v[42:43], v[46:47], off offset:512
	global_load_dwordx2 v[40:41], v[46:47], off offset:1024
	s_nop 0
	global_load_dwordx2 v[36:37], v[46:47], off offset:1536
	s_mov_b32 s7, s8
	v_cmp_gt_u32_e64 s[8:9], 16, v74
	v_mov_b32_e32 v75, -1
	v_lshlrev_b32_e32 v38, 11, v74
	v_mov_b32_e32 v82, v35
	v_mov_b32_e32 v81, -1
	v_writelane_b32 v253, s27, 39
	s_and_saveexec_b64 s[24:25], s[8:9]
	s_cbranch_execz .LBB0_815
	v_readlane_b32 s0, v253, 34
	v_readlane_b32 s1, v253, 35
	s_mov_b32 s4, s0
	s_ashr_i32 s0, s0, 11
	s_ashr_i32 s1, s0, 31
	s_lshl_b64 s[0:1], s[0:1], 15
	s_and_b32 s4, s4, 0x7ff
	s_or_b32 s0, s0, s4
	s_ashr_i32 s4, s68, 11
	s_ashr_i32 s5, s4, 31
	s_lshl_b64 s[4:5], s[4:5], 15
	s_and_b32 s6, s68, 0x7ff
	s_or_b32 s4, s4, s6
	v_or_b32_e32 v46, s4, v38
	v_mov_b32_e32 v47, s5
	v_lshl_add_u64 v[48:49], v[46:47], 1, s[22:23]
	v_lshl_add_u64 v[46:47], v[46:47], 2, s[18:19]
	global_load_sshort v81, v[48:49], off
	global_load_dword v82, v[46:47], off
	v_or_b32_e32 v46, s0, v38
	v_mov_b32_e32 v47, s1
	v_lshl_add_u64 v[48:49], v[46:47], 1, s[22:23]
	v_lshl_add_u64 v[46:47], v[46:47], 2, s[18:19]
	global_load_sshort v75, v[48:49], off
	global_load_dword v35, v[46:47], off

.LBB0_817:
	v_mov_b32_e32 v82, v71
	v_mov_b32_e32 v83, v68
	v_mov_b32_e32 v84, v70
	v_mov_b32_e32 v85, v69
	v_pk_add_f32 v[82:83], v[82:83], v[84:85]
	v_mov_b32_e32 v84, v67
	v_mov_b32_e32 v85, v62
	v_mov_b32_e32 v86, v66
	v_mov_b32_e32 v87, v63
	v_pk_add_f32 v[84:85], v[84:85], v[86:87]
	v_add_f32_e32 v34, v82, v83
	v_pk_add_f32 v[84:85], v[84:85], v[84:85] op_sel_hi:[0,1]
	v_add_f32_e32 v83, 0, v34
	v_add_f32_e32 v87, v64, v65
	v_add_f32_e32 v89, v60, v61
	v_mov_b32_e32 v86, v58
	v_mov_b32_e32 v88, v59
	v_mov_b32_e32 v84, v72
	v_mov_b32_e32 v82, v73
	v_pk_add_f32 v[86:87], v[86:87], v[88:89]
	v_pk_add_f32 v[82:83], v[84:85], v[82:83]
	s_ashr_i32 s29, s28, 31
	v_pk_add_f32 v[82:83], v[86:87], v[82:83]
	s_nop 0
	v_add_f32_e32 v34, v82, v83
	s_nop 1
	v_add_f32_dpp v34, v34, v34 quad_perm:[1,0,3,2] row_mask:0xf bank_mask:0xf bound_ctrl:1
	s_nop 1
	v_add_f32_dpp v34, v34, v34 quad_perm:[2,3,0,1] row_mask:0xf bank_mask:0xf bound_ctrl:1
	s_nop 1
	v_add_f32_dpp v34, v34, v34 row_half_mirror row_mask:0xf bank_mask:0xf bound_ctrl:1
	s_nop 1
	v_add_f32_dpp v34, v34, v34 row_mirror row_mask:0xf bank_mask:0xf bound_ctrl:1
	s_nop 0
	v_readlane_b32 s6, v34, 16
	v_readlane_b32 s10, v34, 48
	v_readlane_b32 s0, v34, 0
	v_readlane_b32 s1, v34, 32
	v_mov_b32_e32 v82, s6
	v_mov_b32_e32 v83, s10
	v_pk_add_f32 v[82:83], s[0:1], v[82:83]
	s_nop 0
	v_add_f32_e32 v46, v82, v83
	v_fmac_f32_e32 v71, 0xba800000, v46
	v_fmac_f32_e32 v70, 0xba800000, v46
	v_fmac_f32_e32 v69, 0xba800000, v46
	v_fmac_f32_e32 v68, 0xba800000, v46
	v_pk_mul_f32 v[82:83], v[68:69], v[68:69]
	v_pk_mul_f32 v[84:85], v[70:71], v[70:71]
	v_fmac_f32_e32 v67, 0xba800000, v46
	v_pk_mov_b32 v[86:87], v[84:85], v[82:83] op_sel:[1,0]
	v_mov_b32_e32 v85, v83
	v_fmac_f32_e32 v66, 0xba800000, v46
	v_fmac_f32_e32 v63, 0xba800000, v46
	v_fmac_f32_e32 v62, 0xba800000, v46
	v_pk_add_f32 v[82:83], v[86:87], v[84:85]
	v_pk_mul_f32 v[84:85], v[62:63], v[62:63]
	v_pk_mul_f32 v[86:87], v[66:67], v[66:67]
	v_fmac_f32_e32 v64, 0xba800000, v46
	v_pk_mov_b32 v[88:89], v[86:87], v[84:85] op_sel:[1,0]
	v_mov_b32_e32 v87, v85
	v_fmac_f32_e32 v65, 0xba800000, v46
	v_fmac_f32_e32 v60, 0xba800000, v46
	v_mul_f32_e32 v34, v64, v64
	v_pk_add_f32 v[84:85], v[88:89], v[86:87]
	v_fmac_f32_e32 v61, 0xba800000, v46
	v_pk_fma_f32 v[86:87], v[64:65], v[64:65], v[34:35] op_sel_hi:[1,1,0]
	v_mul_f32_e32 v34, v60, v60
	v_pk_add_f32 v[82:83], v[82:83], v[82:83] op_sel_hi:[0,1]
	v_pk_add_f32 v[84:85], v[84:85], v[84:85] op_sel_hi:[0,1]
	v_pk_fma_f32 v[88:89], v[60:61], v[60:61], v[34:35] op_sel_hi:[1,1,0]
	v_fmamk_f32 v73, v46, 0xba800000, v73
	v_fmamk_f32 v72, v46, 0xba800000, v72
	v_fmamk_f32 v59, v46, 0xba800000, v59
	v_fmac_f32_e32 v58, 0xba800000, v46
	v_mul_f32_e32 v86, v58, v58
	v_mul_f32_e32 v88, v59, v59
	v_mul_f32_e32 v82, v72, v72
	v_mul_f32_e32 v84, v73, v73
	v_pk_add_f32 v[86:87], v[86:87], v[88:89]
	v_pk_add_f32 v[82:83], v[82:83], v[84:85]
	s_nop 0
	v_pk_add_f32 v[82:83], v[86:87], v[82:83]
	s_nop 0
	v_add_f32_e32 v34, v82, v83
	s_nop 1
	v_add_f32_dpp v34, v34, v34 quad_perm:[1,0,3,2] row_mask:0xf bank_mask:0xf bound_ctrl:1
	s_nop 1
	v_add_f32_dpp v34, v34, v34 quad_perm:[2,3,0,1] row_mask:0xf bank_mask:0xf bound_ctrl:1
	s_nop 1
	v_add_f32_dpp v34, v34, v34 row_half_mirror row_mask:0xf bank_mask:0xf bound_ctrl:1
	s_nop 1
	v_add_f32_dpp v34, v34, v34 row_mirror row_mask:0xf bank_mask:0xf bound_ctrl:1
	s_nop 0
	v_readlane_b32 s6, v34, 16
	v_readlane_b32 s10, v34, 48
	v_readlane_b32 s0, v34, 0
	v_readlane_b32 s1, v34, 32
	v_mov_b32_e32 v82, s6
	v_mov_b32_e32 v83, s10
	v_pk_add_f32 v[82:83], s[0:1], v[82:83]
	s_mov_b32 s0, 0xf800000
	v_add_f32_e32 v34, v82, v83
	v_fmamk_f32 v34, v34, 0x3a800000, v76
	v_mul_f32_e32 v46, 0x4f800000, v34
	v_cmp_gt_f32_e32 vcc, s0, v34
	s_nop 1
	v_cndmask_b32_e32 v34, v34, v46, vcc
	v_sqrt_f32_e32 v46, v34
	s_nop 0
	v_add_u32_e32 v81, -1, v46
	v_fma_f32 v82, -v81, v46, v34
	v_cmp_ge_f32_e64 s[10:11], 0, v82
	v_add_u32_e32 v82, 1, v46
	s_nop 0
	v_cndmask_b32_e64 v81, v46, v81, s[10:11]
	v_fma_f32 v46, -v82, v46, v34
	v_cmp_lt_f32_e64 s[10:11], 0, v46
	s_nop 1
	v_cndmask_b32_e64 v46, v81, v82, s[10:11]
	v_mul_f32_e32 v81, 0x37800000, v46
	v_cndmask_b32_e32 v46, v46, v81, vcc
	v_cmp_class_f32_e32 vcc, v34, v77
	s_nop 1
	v_cndmask_b32_e32 v34, v46, v34, vcc
	v_div_scale_f32 v46, s[0:1], v34, v34, 1.0
	v_rcp_f32_e32 v81, v46
	s_lshl_b64 s[0:1], s[28:29], 11
	s_sub_i32 s28, s26, s33
	s_cmp_gt_i32 s28, 0xffff
	v_fma_f32 v82, -v46, v81, 1.0
	v_fmac_f32_e32 v81, v82, v81
	v_div_scale_f32 v82, vcc, 1.0, v34, 1.0
	v_mul_f32_e32 v83, v82, v81
	v_fma_f32 v84, -v46, v83, v82
	v_fmac_f32_e32 v83, v84, v81
	v_fma_f32 v46, -v46, v83, v82
	v_div_fmas_f32 v46, v46, v81, v83
	v_div_fixup_f32 v34, v46, v34, 1.0
	v_pk_mul_f32 v[66:67], v[66:67], v[34:35] op_sel_hi:[1,0]
	v_pk_mul_f32 v[62:63], v[62:63], v[34:35] op_sel_hi:[1,0]
	v_pk_fma_f32 v[66:67], v[10:11], v[66:67], v[18:19]
	v_pk_fma_f32 v[62:63], v[12:13], v[62:63], v[20:21]
	v_cvt_pk_bf16_f32 v66, v66, v67
	v_cvt_pk_bf16_f32 v67, v62, v63
	v_pk_mul_f32 v[62:63], v[64:65], v[34:35] op_sel_hi:[1,0]
	v_pk_mul_f32 v[60:61], v[60:61], v[34:35] op_sel_hi:[1,0]
	v_pk_fma_f32 v[62:63], v[14:15], v[62:63], v[22:23]
	v_pk_fma_f32 v[60:61], v[16:17], v[60:61], v[24:25]
	v_pk_mul_f32 v[70:71], v[70:71], v[34:35] op_sel_hi:[1,0]
	v_pk_mul_f32 v[68:69], v[68:69], v[34:35] op_sel_hi:[1,0]
	v_cvt_pk_bf16_f32 v62, v62, v63
	v_cvt_pk_bf16_f32 v63, v60, v61
	v_pk_mul_f32 v[58:59], v[58:59], v[34:35] op_sel_hi:[1,0]
	v_pk_mul_f32 v[60:61], v[72:73], v[34:35] op_sel_hi:[1,0]
	v_pk_fma_f32 v[68:69], v[4:5], v[68:69], v[8:9]
	v_pk_fma_f32 v[70:71], v[2:3], v[70:71], v[6:7]
	v_pk_fma_f32 v[60:61], v[28:29], v[60:61], v[32:33]
	v_pk_fma_f32 v[58:59], v[26:27], v[58:59], v[30:31]
	v_cvt_pk_bf16_f32 v70, v70, v71
	v_cvt_pk_bf16_f32 v71, v68, v69
	v_lshl_add_u64 v[68:69], v[48:49], 0, s[0:1]
	v_cvt_pk_bf16_f32 v58, v58, v59
	v_cvt_pk_bf16_f32 v59, v60, v61
	global_store_dwordx2 v[68:69], v[62:63], off offset:1024
	global_store_dwordx2 v[68:69], v[58:59], off offset:1536
	v_mov_b32_e32 v64, v44
	v_mov_b32_e32 v65, v45
	v_mov_b32_e32 v62, v42
	v_mov_b32_e32 v63, v43
	v_mov_b32_e32 v60, v40
	v_mov_b32_e32 v61, v41
	v_mov_b32_e32 v58, v36
	v_mov_b32_e32 v59, v37
	s_waitcnt vmcnt(0) lgkmcnt(0)
	v_mov_b64_e32 v[36:37], v[50:51]
	v_mov_b64_e32 v[40:41], v[52:53]
	v_mov_b64_e32 v[42:43], v[54:55]
	v_mov_b64_e32 v[44:45], v[56:57]
	v_mov_b32_e32 v81, v75
	v_mov_b32_e32 v75, v79
	v_mov_b32_e32 v82, v35
	v_mov_b32_e32 v35, v80
	global_store_dwordx2 v[68:69], v[70:71], off
	global_store_dwordx2 v[68:69], v[66:67], off offset:512
	s_cbranch_scc1 .LBB0_827
.LBB0_818:
	s_add_i32 s26, s28, s94
	s_cmp_gt_i32 s26, 0xffff
	v_mov_b32_e32 v80, v35
	s_cbranch_scc1 .LBB0_822
	s_ashr_i32 s27, s26, 31
	s_lshl_b64 s[0:1], s[26:27], 11
	v_lshl_add_u64 v[50:51], v[48:49], 0, s[0:1]
	global_load_dwordx2 v[56:57], v[50:51], off
	global_load_dwordx2 v[54:55], v[50:51], off offset:512
	global_load_dwordx2 v[52:53], v[50:51], off offset:1024
	s_nop 0
	global_load_dwordx2 v[50:51], v[50:51], off offset:1536
	v_mov_b32_e32 v79, v75
	v_mov_b32_e32 v80, v35
	s_and_saveexec_b64 s[10:11], s[8:9]
	s_cbranch_execz .LBB0_821
	s_ashr_i32 s0, s26, 11
	s_ashr_i32 s1, s0, 31
	s_lshl_b64 s[0:1], s[0:1], 15
	v_or_b32_e32 v34, s0, v38
	s_and_b32 s0, s26, 0x7ff
	v_mov_b32_e32 v67, s1
	v_or_b32_e32 v66, s0, v34
	v_lshl_add_u64 v[68:69], v[66:67], 1, s[22:23]
	v_lshl_add_u64 v[66:67], v[66:67], 2, s[18:19]
	global_load_sshort v79, v[68:69], off
	global_load_dword v80, v[66:67], off

.LBB0_824:
	s_add_u32 s36, s34, -1
	s_addc_u32 s37, s35, -1
	s_lshl_b32 s11, s11, 5
	s_and_b64 vcc, s[36:37], s[34:35]
	s_add_i32 s34, s11, s6
	s_ashr_i32 s35, s34, 31
	s_ashr_i32 s31, s30, 31
	s_lshl_b64 s[34:35], s[34:35], 18
	s_lshl_b64 s[30:31], s[30:31], 10
	s_add_u32 s11, s4, s34
	s_addc_u32 s21, s5, s35
	s_add_u32 s30, s11, s30
	s_addc_u32 s31, s21, s31
	s_lshl_b32 s1, s1, 5
	s_add_i32 s34, s1, s6
	s_ashr_i32 s35, s34, 31
	s_ashr_i32 s11, s10, 31
	v_lshlrev_b32_e32 v46, 2, v74
	s_lshl_b64 s[34:35], s[34:35], 18
	s_lshl_b64 s[10:11], s[10:11], 10
	v_lshl_add_u64 v[84:85], s[30:31], 0, v[46:47]
	s_add_u32 s1, s4, s34
	global_load_dword v83, v[84:85], off
	s_addc_u32 s21, s5, s35
	s_add_u32 s10, s1, s10
	s_addc_u32 s11, s21, s11
	v_lshl_add_u64 v[86:87], s[10:11], 0, v[46:47]
	global_load_dword v90, v[86:87], off
	global_load_dword v92, v[84:85], off offset:256
	global_load_dword v93, v[86:87], off offset:256
	global_load_dword v94, v[84:85], off offset:512
	global_load_dword v95, v[86:87], off offset:512
	global_load_dword v96, v[84:85], off offset:768
	global_load_dword v97, v[86:87], off offset:768
	v_mul_f32_e32 v46, s0, v78
	s_cmp_eq_u64 vcc, 0
	s_waitcnt vmcnt(0) lgkmcnt(0)
	v_cvt_pk_f32_fp8_e32 v[88:89], v90
	v_cvt_pk_f32_fp8_sdwa v[90:91], v90 src0_sel:WORD_1
	v_cvt_pk_f32_fp8_e32 v[84:85], v83
	v_cvt_pk_f32_fp8_sdwa v[86:87], v83 src0_sel:WORD_1
	v_pk_mul_f32 v[88:89], v[34:35], v[88:89] op_sel_hi:[0,1]
	v_pk_mul_f32 v[90:91], v[34:35], v[90:91] op_sel_hi:[0,1]
	v_pk_fma_f32 v[84:85], v[46:47], v[84:85], v[88:89] op_sel_hi:[0,1,1]
	v_pk_fma_f32 v[86:87], v[46:47], v[86:87], v[90:91] op_sel_hi:[0,1,1]
	v_cvt_pk_f32_fp8_e32 v[88:89], v93
	v_cvt_pk_f32_fp8_sdwa v[90:91], v93 src0_sel:WORD_1
	v_pk_add_f32 v[68:69], v[68:69], v[86:87]
	v_pk_add_f32 v[70:71], v[70:71], v[84:85]
	v_cvt_pk_f32_fp8_e32 v[84:85], v92
	v_cvt_pk_f32_fp8_sdwa v[86:87], v92 src0_sel:WORD_1
	v_pk_mul_f32 v[90:91], v[34:35], v[90:91] op_sel_hi:[0,1]
	v_pk_mul_f32 v[88:89], v[34:35], v[88:89] op_sel_hi:[0,1]
	v_pk_fma_f32 v[84:85], v[46:47], v[84:85], v[88:89] op_sel_hi:[0,1,1]
	v_pk_fma_f32 v[86:87], v[46:47], v[86:87], v[90:91] op_sel_hi:[0,1,1]
	v_cvt_pk_f32_fp8_e32 v[88:89], v95
	v_cvt_pk_f32_fp8_sdwa v[90:91], v95 src0_sel:WORD_1
	v_pk_add_f32 v[62:63], v[62:63], v[86:87]
	v_pk_add_f32 v[66:67], v[66:67], v[84:85]
	v_cvt_pk_f32_fp8_e32 v[84:85], v94
	v_cvt_pk_f32_fp8_sdwa v[86:87], v94 src0_sel:WORD_1
	v_pk_mul_f32 v[90:91], v[34:35], v[90:91] op_sel_hi:[0,1]
	v_pk_mul_f32 v[88:89], v[34:35], v[88:89] op_sel_hi:[0,1]
	v_pk_fma_f32 v[84:85], v[46:47], v[84:85], v[88:89] op_sel_hi:[0,1,1]
	v_pk_fma_f32 v[86:87], v[46:47], v[86:87], v[90:91] op_sel_hi:[0,1,1]
	v_cvt_pk_f32_fp8_e32 v[88:89], v97
	v_cvt_pk_f32_fp8_sdwa v[90:91], v97 src0_sel:WORD_1
	v_pk_add_f32 v[60:61], v[60:61], v[86:87]
	v_pk_add_f32 v[64:65], v[64:65], v[84:85]
	v_cvt_pk_f32_fp8_e32 v[84:85], v96
	v_cvt_pk_f32_fp8_sdwa v[86:87], v96 src0_sel:WORD_1
	v_pk_mul_f32 v[90:91], v[34:35], v[90:91] op_sel_hi:[0,1]
	v_pk_mul_f32 v[88:89], v[34:35], v[88:89] op_sel_hi:[0,1]
	v_pk_fma_f32 v[84:85], v[46:47], v[84:85], v[88:89] op_sel_hi:[0,1,1]
	v_pk_fma_f32 v[86:87], v[46:47], v[86:87], v[90:91] op_sel_hi:[0,1,1]
	v_pk_add_f32 v[72:73], v[72:73], v[86:87]
	v_pk_add_f32 v[58:59], v[58:59], v[84:85]
	s_cbranch_scc1 .LBB0_817

.LBB0_830:
	s_mul_hi_i32 s0, s21, 0x2aaaaaab
	s_lshr_b32 s1, s0, 31
	s_ashr_i32 s0, s0, 8
	s_add_i32 s16, s0, s1
	s_mul_i32 s0, s16, 0xfffffa00
	s_add_i32 s24, s21, s0
	s_lshr_b32 s0, s24, 22
	s_and_b32 s0, s0, 0x1ff
	s_add_i32 s25, s24, s0
	s_and_b32 s0, s25, 0xfe00
	s_sub_i32 s0, s24, s0
	s_sext_i32_i16 s1, s0
	s_bfe_u32 s1, s1, 0x5001a
	s_add_i32 s1, s0, s1
	s_sext_i32_i16 s8, s1
	s_and_b32 s1, s1, 0xffe0
	s_lshl_b32 s23, s8, 1
	s_sub_i32 s0, s0, s1
	s_andn2_b32 s23, s23, 63
	s_sext_i32_i16 s22, s0
	s_lshl_b32 s8, s22, 5
	v_or_b32_e32 v20, s23, v26
	s_mov_b64 s[18:19], -1
	s_cmpk_gt_i32 s24, 0x3ff
	v_ashrrev_i32_e32 v21, 31, v20
	v_or_b32_e32 v18, 8, v20
	v_or_b32_e32 v16, 16, v20
	v_or_b32_e32 v14, 24, v20
	v_or_b32_e32 v12, 32, v20
	v_or_b32_e32 v10, 40, v20
	v_or_b32_e32 v8, 48, v20
	v_or_b32_e32 v6, 56, v20
	s_cbranch_scc0 .LBB0_832
	s_ashr_i32 s17, s16, 31
	s_lshl_b64 s[0:1], s[16:17], 20
	s_lshl_b64 s[18:19], s[16:17], 22
	s_add_u32 s17, s10, s18
	s_addc_u32 s18, s11, s19
	s_add_u32 s19, s6, s0
	s_addc_u32 s26, s7, s1
	s_ashr_i32 s9, s8, 31
	s_lshl_b64 s[0:1], s[8:9], 2
	s_add_u32 s0, s17, s0
	s_addc_u32 s1, s18, s1
	v_lshl_add_u64 v[72:73], s[0:1], 0, v[2:3]
	v_lshlrev_b64 v[22:23], 12, v[20:21]
	v_lshl_add_u64 v[22:23], v[72:73], 0, v[22:23]
	v_ashrrev_i32_e32 v19, 31, v18
	global_load_dwordx4 v[22:25], v[22:23], off nt
	v_lshlrev_b64 v[48:49], 12, v[18:19]
	v_lshl_add_u64 v[48:49], v[72:73], 0, v[48:49]
	v_ashrrev_i32_e32 v17, 31, v16
	global_load_dwordx4 v[48:51], v[48:49], off nt
	v_lshlrev_b64 v[52:53], 12, v[16:17]
	v_lshl_add_u64 v[52:53], v[72:73], 0, v[52:53]
	v_ashrrev_i32_e32 v15, 31, v14
	global_load_dwordx4 v[52:55], v[52:53], off nt
	v_lshlrev_b64 v[56:57], 12, v[14:15]
	v_lshl_add_u64 v[56:57], v[72:73], 0, v[56:57]
	v_ashrrev_i32_e32 v13, 31, v12
	global_load_dwordx4 v[56:59], v[56:57], off nt
	v_lshlrev_b64 v[60:61], 12, v[12:13]
	v_lshl_add_u64 v[60:61], v[72:73], 0, v[60:61]
	v_ashrrev_i32_e32 v11, 31, v10
	global_load_dwordx4 v[60:63], v[60:61], off nt
	v_lshlrev_b64 v[64:65], 12, v[10:11]
	v_lshl_add_u64 v[64:65], v[72:73], 0, v[64:65]
	v_ashrrev_i32_e32 v9, 31, v8
	global_load_dwordx4 v[64:67], v[64:65], off nt
	v_lshlrev_b64 v[68:69], 12, v[8:9]
	v_lshl_add_u64 v[68:69], v[72:73], 0, v[68:69]
	v_ashrrev_i32_e32 v7, 31, v6
	global_load_dwordx4 v[68:71], v[68:69], off nt
	v_lshlrev_b64 v[74:75], 12, v[6:7]
	v_lshl_add_u64 v[72:73], v[72:73], 0, v[74:75]
	global_load_dwordx4 v[72:75], v[72:73], off nt
	s_ashr_i32 s1, s23, 31
	s_add_u32 s0, s19, s23
	s_addc_u32 s1, s26, s1
	s_waitcnt vmcnt(0)
	ds_write2_b32 v31, v22, v23 offset1:1
	ds_write2_b32 v31, v24, v25 offset0:2 offset1:3
	s_waitcnt vmcnt(6)
	ds_write2_b32 v32, v48, v49 offset1:1
	ds_write2_b32 v33, v50, v51 offset1:1
	s_waitcnt vmcnt(5)
	ds_write2_b32 v34, v52, v53 offset1:1
	ds_write2_b32 v35, v54, v55 offset1:1
	s_waitcnt vmcnt(4)
	ds_write2_b32 v36, v56, v57 offset1:1
	ds_write2_b32 v37, v58, v59 offset1:1
	s_waitcnt vmcnt(3)
	ds_write2_b32 v38, v60, v61 offset1:1
	ds_write2_b32 v39, v62, v63 offset1:1
	s_waitcnt vmcnt(2)
	ds_write2_b32 v40, v64, v65 offset1:1
	ds_write2_b32 v41, v66, v67 offset1:1
	s_waitcnt vmcnt(1)
	ds_write2_b32 v42, v68, v69 offset1:1
	ds_write2_b32 v43, v70, v71 offset1:1
	s_waitcnt vmcnt(0)
	ds_write2_b32 v44, v72, v73 offset1:1
	ds_write2_b32 v45, v74, v75 offset1:1
	s_waitcnt lgkmcnt(0)
	ds_read_b32 v7, v30
	ds_read_b32 v9, v30 offset:132
	ds_read_b32 v11, v30 offset:264
	ds_read_b32 v13, v30 offset:396
	v_mov_b32_e32 v24, v3
	s_waitcnt lgkmcnt(0)
	v_mul_f32_e32 v7, 0x43000000, v7
	s_waitcnt lgkmcnt(2)
	v_mul_f32_e32 v9, 0x43000000, v9
	v_med3_f32 v7, v7, s20, v46
	v_med3_f32 v9, v9, s20, v46
	v_cvt_pk_fp8_f32 v24, v7, v9
	s_waitcnt lgkmcnt(1)
	v_mul_f32_e32 v11, 0x43000000, v11
	s_waitcnt lgkmcnt(0)
	v_mul_f32_e32 v13, 0x43000000, v13
	v_med3_f32 v7, v11, s20, v46
	v_med3_f32 v9, v13, s20, v46
	v_cvt_pk_fp8_f32 v24, v7, v9 op_sel:[0,0,1]
	ds_read_b32 v7, v30 offset:528
	ds_read_b32 v9, v30 offset:660
	ds_read_b32 v11, v30 offset:792
	ds_read_b32 v13, v30 offset:924
	v_mov_b32_e32 v25, v3
	s_waitcnt lgkmcnt(3)
	v_mul_f32_e32 v7, 0x43000000, v7
	s_waitcnt lgkmcnt(2)
	v_mul_f32_e32 v9, 0x43000000, v9
	v_med3_f32 v7, v7, s20, v46
	v_med3_f32 v9, v9, s20, v46
	v_cvt_pk_fp8_f32 v25, v7, v9
	s_waitcnt lgkmcnt(1)
	v_mul_f32_e32 v11, 0x43000000, v11
	s_waitcnt lgkmcnt(0)
	v_mul_f32_e32 v13, 0x43000000, v13
	v_med3_f32 v7, v11, s20, v46
	v_med3_f32 v9, v13, s20, v46
	v_cvt_pk_fp8_f32 v25, v7, v9 op_sel:[0,0,1]
	v_or_b32_e32 v48, s8, v26
	v_ashrrev_i32_e32 v49, 31, v48
	v_lshl_add_u64 v[22:23], s[0:1], 0, v[4:5]
	v_lshlrev_b64 v[48:49], 10, v[48:49]
	v_lshl_add_u64 v[48:49], v[22:23], 0, v[48:49]
	global_store_dwordx2 v[48:49], v[24:25], off
	ds_read_b32 v7, v30 offset:32
	ds_read_b32 v9, v30 offset:164
	ds_read_b32 v11, v30 offset:296
	ds_read_b32 v13, v30 offset:428
	v_mov_b32_e32 v24, v3
	s_waitcnt lgkmcnt(0)
	v_mul_f32_e32 v7, 0x43000000, v7
	v_mul_f32_e32 v9, 0x43000000, v9
	v_med3_f32 v7, v7, s20, v46
	v_med3_f32 v9, v9, s20, v46
	v_cvt_pk_fp8_f32 v24, v7, v9
	v_mul_f32_e32 v11, 0x43000000, v11
	v_mul_f32_e32 v13, 0x43000000, v13
	v_med3_f32 v7, v11, s20, v46
	v_med3_f32 v9, v13, s20, v46
	v_cvt_pk_fp8_f32 v24, v7, v9 op_sel:[0,0,1]
	ds_read_b32 v7, v30 offset:560
	ds_read_b32 v9, v30 offset:692
	ds_read_b32 v11, v30 offset:824
	ds_read_b32 v13, v30 offset:956
	v_mov_b32_e32 v25, v3
	s_waitcnt lgkmcnt(0)
	v_mul_f32_e32 v7, 0x43000000, v7
	v_mul_f32_e32 v9, 0x43000000, v9
	v_med3_f32 v7, v7, s20, v46
	v_med3_f32 v9, v9, s20, v46
	v_cvt_pk_fp8_f32 v25, v7, v9
	v_mul_f32_e32 v11, 0x43000000, v11
	v_mul_f32_e32 v13, 0x43000000, v13
	v_med3_f32 v7, v11, s20, v46
	v_med3_f32 v9, v13, s20, v46
	v_cvt_pk_fp8_f32 v25, v7, v9 op_sel:[0,0,1]
	v_or_b32_e32 v48, s8, v27
	v_ashrrev_i32_e32 v49, 31, v48
	v_lshlrev_b64 v[48:49], 10, v[48:49]
	v_lshl_add_u64 v[48:49], v[22:23], 0, v[48:49]
	global_store_dwordx2 v[48:49], v[24:25], off
	ds_read_b32 v7, v30 offset:64
	ds_read_b32 v9, v30 offset:196
	ds_read_b32 v11, v30 offset:328
	ds_read_b32 v13, v30 offset:460
	v_mov_b32_e32 v24, v3
	s_waitcnt lgkmcnt(0)
	v_mul_f32_e32 v7, 0x43000000, v7
	v_mul_f32_e32 v9, 0x43000000, v9
	v_med3_f32 v7, v7, s20, v46
	v_med3_f32 v9, v9, s20, v46
	v_cvt_pk_fp8_f32 v24, v7, v9
	v_mul_f32_e32 v11, 0x43000000, v11
	v_mul_f32_e32 v13, 0x43000000, v13
	v_med3_f32 v7, v11, s20, v46
	v_med3_f32 v9, v13, s20, v46
	v_cvt_pk_fp8_f32 v24, v7, v9 op_sel:[0,0,1]
	ds_read_b32 v7, v30 offset:592
	ds_read_b32 v9, v30 offset:724
	ds_read_b32 v11, v30 offset:856
	ds_read_b32 v13, v30 offset:988
	v_mov_b32_e32 v25, v3
	s_waitcnt lgkmcnt(0)
	v_mul_f32_e32 v7, 0x43000000, v7
	v_mul_f32_e32 v9, 0x43000000, v9
	v_med3_f32 v7, v7, s20, v46
	v_med3_f32 v9, v9, s20, v46
	v_cvt_pk_fp8_f32 v25, v7, v9
	v_mul_f32_e32 v11, 0x43000000, v11
	v_mul_f32_e32 v13, 0x43000000, v13
	v_med3_f32 v7, v11, s20, v46
	v_med3_f32 v9, v13, s20, v46
	v_cvt_pk_fp8_f32 v25, v7, v9 op_sel:[0,0,1]
	v_or_b32_e32 v48, s8, v28
	v_ashrrev_i32_e32 v49, 31, v48
	v_lshlrev_b64 v[48:49], 10, v[48:49]
	v_lshl_add_u64 v[48:49], v[22:23], 0, v[48:49]
	global_store_dwordx2 v[48:49], v[24:25], off
	ds_read_b32 v7, v30 offset:96
	ds_read_b32 v9, v30 offset:228
	ds_read_b32 v11, v30 offset:360
	ds_read_b32 v13, v30 offset:492
	v_mov_b32_e32 v24, v3
	s_waitcnt lgkmcnt(0)
	v_mul_f32_e32 v7, 0x43000000, v7
	v_mul_f32_e32 v9, 0x43000000, v9
	v_med3_f32 v7, v7, s20, v46
	v_med3_f32 v9, v9, s20, v46
	v_cvt_pk_fp8_f32 v24, v7, v9
	v_mul_f32_e32 v11, 0x43000000, v11
	v_mul_f32_e32 v13, 0x43000000, v13
	v_med3_f32 v7, v11, s20, v46
	v_med3_f32 v9, v13, s20, v46
	v_cvt_pk_fp8_f32 v24, v7, v9 op_sel:[0,0,1]
	ds_read_b32 v7, v30 offset:624
	ds_read_b32 v9, v30 offset:756
	ds_read_b32 v11, v30 offset:888
	ds_read_b32 v13, v30 offset:1020
	v_mov_b32_e32 v25, v3
	s_waitcnt lgkmcnt(0)
	v_mul_f32_e32 v7, 0x43000000, v7
	v_mul_f32_e32 v9, 0x43000000, v9
	v_med3_f32 v7, v7, s20, v46
	v_med3_f32 v9, v9, s20, v46
	v_cvt_pk_fp8_f32 v25, v7, v9
	v_mul_f32_e32 v11, 0x43000000, v11
	v_mul_f32_e32 v13, 0x43000000, v13
	v_med3_f32 v7, v11, s20, v46
	v_med3_f32 v9, v13, s20, v46
	v_cvt_pk_fp8_f32 v25, v7, v9 op_sel:[0,0,1]
	v_or_b32_e32 v48, s8, v29
	v_ashrrev_i32_e32 v49, 31, v48
	v_lshlrev_b64 v[48:49], 10, v[48:49]
	v_lshl_add_u64 v[22:23], v[22:23], 0, v[48:49]
	global_store_dwordx2 v[22:23], v[24:25], off
	s_waitcnt lgkmcnt(0)
	s_cbranch_execnz .LBB0_829
	s_branch .LBB0_833

.LBB0_833:
	s_sext_i32_i16 s0, s25
	s_lshr_b32 s0, s0, 9
	s_addk_i32 s24, 0x1ff
	s_cmpk_lt_u32 s24, 0x3ff
	s_cselect_b32 s9, s13, s15
	s_cselect_b32 s19, s12, s14
	s_ashr_i32 s17, s16, 31
	s_sext_i32_i16 s18, s0
	s_lshl_b64 s[0:1], s[16:17], 22
	s_add_u32 s19, s19, s0
	s_addc_u32 s24, s9, s1
	s_lshl_b64 s[0:1], s[16:17], 21
	s_add_u32 s16, s4, s0
	s_addc_u32 s17, s5, s1
	s_ashr_i32 s9, s8, 31
	s_lshl_b64 s[0:1], s[8:9], 2
	s_add_u32 s0, s19, s0
	s_addc_u32 s1, s24, s1
	v_lshl_add_u64 v[22:23], s[0:1], 0, v[2:3]
	s_mov_b64 s[0:1], 0x4000000
	v_lshl_add_u64 v[24:25], v[22:23], 0, s[0:1]
	v_lshlrev_b64 v[20:21], 12, v[20:21]
	v_lshl_add_u64 v[20:21], v[24:25], 0, v[20:21]
	v_ashrrev_i32_e32 v19, 31, v18
	global_load_dwordx4 v[20:23], v[20:21], off nt
	v_lshlrev_b64 v[18:19], 12, v[18:19]
	v_lshl_add_u64 v[18:19], v[24:25], 0, v[18:19]
	v_ashrrev_i32_e32 v17, 31, v16
	global_load_dwordx4 v[48:51], v[18:19], off nt
	v_lshlrev_b64 v[16:17], 12, v[16:17]
	v_lshl_add_u64 v[16:17], v[24:25], 0, v[16:17]
	v_ashrrev_i32_e32 v15, 31, v14
	global_load_dwordx4 v[16:19], v[16:17], off nt
	v_lshlrev_b64 v[14:15], 12, v[14:15]
	v_lshl_add_u64 v[14:15], v[24:25], 0, v[14:15]
	v_ashrrev_i32_e32 v13, 31, v12
	global_load_dwordx4 v[52:55], v[14:15], off nt
	v_lshlrev_b64 v[12:13], 12, v[12:13]
	v_lshl_add_u64 v[12:13], v[24:25], 0, v[12:13]
	v_ashrrev_i32_e32 v11, 31, v10
	global_load_dwordx4 v[12:15], v[12:13], off nt
	v_lshlrev_b64 v[10:11], 12, v[10:11]
	v_lshl_add_u64 v[10:11], v[24:25], 0, v[10:11]
	v_ashrrev_i32_e32 v9, 31, v8
	global_load_dwordx4 v[56:59], v[10:11], off nt
	v_lshlrev_b64 v[8:9], 12, v[8:9]
	v_lshl_add_u64 v[8:9], v[24:25], 0, v[8:9]
	v_ashrrev_i32_e32 v7, 31, v6
	global_load_dwordx4 v[8:11], v[8:9], off nt
	v_lshlrev_b64 v[6:7], 12, v[6:7]
	v_lshl_add_u64 v[6:7], v[24:25], 0, v[6:7]
	global_load_dwordx4 v[60:63], v[6:7], off nt
	s_lshl_b32 s1, s18, 7
	s_ashr_i32 s0, s23, 31
	s_add_u32 s16, s16, s23
	s_addc_u32 s17, s17, s0
	s_lshl_b32 s0, s22, 6
	s_and_b32 s0, s0, 0xffffff00
	s_add_i32 s0, s0, s1
	s_and_b32 s1, s8, 0x60
	s_or_b32 s8, s0, s1
	v_lshl_add_u64 v[6:7], s[16:17], 0, v[4:5]
	s_waitcnt vmcnt(0)
	ds_write2_b32 v31, v20, v21 offset1:1
	ds_write2_b32 v31, v22, v23 offset0:2 offset1:3
	ds_write2_b32 v32, v48, v49 offset1:1
	ds_write2_b32 v33, v50, v51 offset1:1
	ds_write2_b32 v34, v16, v17 offset1:1
	ds_write2_b32 v35, v18, v19 offset1:1
	ds_write2_b32 v36, v52, v53 offset1:1
	ds_write2_b32 v37, v54, v55 offset1:1
	ds_write2_b32 v38, v12, v13 offset1:1
	ds_write2_b32 v39, v14, v15 offset1:1
	ds_write2_b32 v40, v56, v57 offset1:1
	ds_write2_b32 v41, v58, v59 offset1:1
	ds_write2_b32 v42, v8, v9 offset1:1
	ds_write2_b32 v43, v10, v11 offset1:1
	ds_write2_b32 v44, v60, v61 offset1:1
	ds_write2_b32 v45, v62, v63 offset1:1
	s_waitcnt lgkmcnt(0)
	ds_read_b32 v8, v30
	ds_read_b32 v9, v30 offset:132
	ds_read_b32 v10, v30 offset:264
	ds_read_b32 v11, v30 offset:396
	s_waitcnt lgkmcnt(0)
	v_mul_f32_e32 v8, 0x42800000, v8
	v_mul_f32_e32 v9, 0x42800000, v9
	v_med3_f32 v12, v8, s20, v46
	v_med3_f32 v9, v9, s20, v46
	v_mov_b32_e32 v8, v3
	v_cvt_pk_fp8_f32 v8, v12, v9
	v_mul_f32_e32 v10, 0x42800000, v10
	v_mul_f32_e32 v11, 0x42800000, v11
	v_med3_f32 v9, v10, s20, v46
	v_med3_f32 v10, v11, s20, v46
	v_cvt_pk_fp8_f32 v8, v9, v10 op_sel:[0,0,1]
	ds_read_b32 v9, v30 offset:528
	ds_read_b32 v10, v30 offset:660
	ds_read_b32 v11, v30 offset:792
	ds_read_b32 v12, v30 offset:924
	s_waitcnt lgkmcnt(3)
	v_mul_f32_e32 v9, 0x42800000, v9
	s_waitcnt lgkmcnt(2)
	v_mul_f32_e32 v10, 0x42800000, v10
	v_med3_f32 v13, v9, s20, v46
	v_med3_f32 v10, v10, s20, v46
	v_mov_b32_e32 v9, v3
	v_cvt_pk_fp8_f32 v9, v13, v10
	s_waitcnt lgkmcnt(1)
	v_mul_f32_e32 v11, 0x42800000, v11
	s_waitcnt lgkmcnt(0)
	v_mul_f32_e32 v12, 0x42800000, v12
	v_med3_f32 v10, v11, s20, v46
	v_med3_f32 v11, v12, s20, v46
	v_cvt_pk_fp8_f32 v9, v10, v11 op_sel:[0,0,1]
	v_or_b32_e32 v10, s8, v26
	v_ashrrev_i32_e32 v11, 31, v10
	v_lshlrev_b64 v[10:11], 10, v[10:11]
	v_lshl_add_u64 v[10:11], v[6:7], 0, v[10:11]
	global_store_dwordx2 v[10:11], v[8:9], off
	ds_read_b32 v8, v30 offset:32
	ds_read_b32 v9, v30 offset:164
	ds_read_b32 v10, v30 offset:296
	ds_read_b32 v11, v30 offset:428
	s_waitcnt lgkmcnt(0)
	v_mul_f32_e32 v8, 0x42800000, v8
	v_mul_f32_e32 v9, 0x42800000, v9
	v_med3_f32 v12, v8, s20, v46
	v_med3_f32 v9, v9, s20, v46
	v_mov_b32_e32 v8, v3
	v_cvt_pk_fp8_f32 v8, v12, v9
	v_mul_f32_e32 v10, 0x42800000, v10
	v_mul_f32_e32 v11, 0x42800000, v11
	v_med3_f32 v9, v10, s20, v46
	v_med3_f32 v10, v11, s20, v46
	v_cvt_pk_fp8_f32 v8, v9, v10 op_sel:[0,0,1]
	ds_read_b32 v9, v30 offset:560
	ds_read_b32 v10, v30 offset:692
	ds_read_b32 v11, v30 offset:824
	ds_read_b32 v12, v30 offset:956
	s_waitcnt lgkmcnt(0)
	v_mul_f32_e32 v9, 0x42800000, v9
	v_mul_f32_e32 v10, 0x42800000, v10
	v_med3_f32 v13, v9, s20, v46
	v_med3_f32 v10, v10, s20, v46
	v_mov_b32_e32 v9, v3
	v_cvt_pk_fp8_f32 v9, v13, v10
	v_mul_f32_e32 v11, 0x42800000, v11
	v_mul_f32_e32 v12, 0x42800000, v12
	v_med3_f32 v10, v11, s20, v46
	v_med3_f32 v11, v12, s20, v46
	v_cvt_pk_fp8_f32 v9, v10, v11 op_sel:[0,0,1]
	v_or_b32_e32 v10, s8, v27
	v_ashrrev_i32_e32 v11, 31, v10
	v_lshlrev_b64 v[10:11], 10, v[10:11]
	v_lshl_add_u64 v[10:11], v[6:7], 0, v[10:11]
	global_store_dwordx2 v[10:11], v[8:9], off
	ds_read_b32 v8, v30 offset:64
	ds_read_b32 v9, v30 offset:196
	ds_read_b32 v10, v30 offset:328
	ds_read_b32 v11, v30 offset:460
	s_waitcnt lgkmcnt(0)
	v_mul_f32_e32 v8, 0x42800000, v8
	v_mul_f32_e32 v9, 0x42800000, v9
	v_med3_f32 v12, v8, s20, v46
	v_med3_f32 v9, v9, s20, v46
	v_mov_b32_e32 v8, v3
	v_cvt_pk_fp8_f32 v8, v12, v9
	v_mul_f32_e32 v10, 0x42800000, v10
	v_mul_f32_e32 v11, 0x42800000, v11
	v_med3_f32 v9, v10, s20, v46
	v_med3_f32 v10, v11, s20, v46
	v_cvt_pk_fp8_f32 v8, v9, v10 op_sel:[0,0,1]
	ds_read_b32 v9, v30 offset:592
	ds_read_b32 v10, v30 offset:724
	ds_read_b32 v11, v30 offset:856
	ds_read_b32 v12, v30 offset:988
	s_waitcnt lgkmcnt(0)
	v_mul_f32_e32 v9, 0x42800000, v9
	v_mul_f32_e32 v10, 0x42800000, v10
	v_med3_f32 v13, v9, s20, v46
	v_med3_f32 v10, v10, s20, v46
	v_mov_b32_e32 v9, v3
	v_cvt_pk_fp8_f32 v9, v13, v10
	v_mul_f32_e32 v11, 0x42800000, v11
	v_mul_f32_e32 v12, 0x42800000, v12
	v_med3_f32 v10, v11, s20, v46
	v_med3_f32 v11, v12, s20, v46
	v_cvt_pk_fp8_f32 v9, v10, v11 op_sel:[0,0,1]
	v_or_b32_e32 v10, s8, v28
	v_ashrrev_i32_e32 v11, 31, v10
	v_lshlrev_b64 v[10:11], 10, v[10:11]
	v_lshl_add_u64 v[10:11], v[6:7], 0, v[10:11]
	global_store_dwordx2 v[10:11], v[8:9], off
	ds_read_b32 v8, v30 offset:96
	ds_read_b32 v9, v30 offset:228
	ds_read_b32 v10, v30 offset:360
	ds_read_b32 v11, v30 offset:492
	s_waitcnt lgkmcnt(0)
	v_mul_f32_e32 v8, 0x42800000, v8
	v_mul_f32_e32 v9, 0x42800000, v9
	v_med3_f32 v12, v8, s20, v46
	v_med3_f32 v9, v9, s20, v46
	v_mov_b32_e32 v8, v3
	v_cvt_pk_fp8_f32 v8, v12, v9
	v_mul_f32_e32 v10, 0x42800000, v10
	v_mul_f32_e32 v11, 0x42800000, v11
	v_med3_f32 v9, v10, s20, v46
	v_med3_f32 v10, v11, s20, v46
	v_cvt_pk_fp8_f32 v8, v9, v10 op_sel:[0,0,1]
	ds_read_b32 v9, v30 offset:624
	ds_read_b32 v10, v30 offset:756
	ds_read_b32 v11, v30 offset:888
	ds_read_b32 v12, v30 offset:1020
	s_waitcnt lgkmcnt(0)
	v_mul_f32_e32 v9, 0x42800000, v9
	v_mul_f32_e32 v10, 0x42800000, v10
	v_med3_f32 v13, v9, s20, v46
	v_med3_f32 v10, v10, s20, v46
	v_mov_b32_e32 v9, v3
	v_cvt_pk_fp8_f32 v9, v13, v10
	v_mul_f32_e32 v11, 0x42800000, v11
	v_mul_f32_e32 v12, 0x42800000, v12
	v_med3_f32 v10, v11, s20, v46
	v_med3_f32 v11, v12, s20, v46
	v_cvt_pk_fp8_f32 v9, v10, v11 op_sel:[0,0,1]
	v_or_b32_e32 v10, s8, v29
	v_ashrrev_i32_e32 v11, 31, v10
	v_lshlrev_b64 v[10:11], 10, v[10:11]
	v_lshl_add_u64 v[6:7], v[6:7], 0, v[10:11]
	global_store_dwordx2 v[6:7], v[8:9], off
	s_waitcnt lgkmcnt(0)
	s_branch .LBB0_829

.LBB0_895:
	ds_read_b128 v[156:159], v152
	ds_read_b128 v[160:163], v152 offset:1024
	ds_read_b128 v[164:167], v152 offset:2048
	ds_read_b128 v[168:171], v152 offset:3072
	s_add_u32 s0, s30, 0xfffc0080
	s_addc_u32 s1, s31, -1
	s_cmp_eq_u32 s55, 12
	s_cselect_b32 s37, s23, s1
	s_cselect_b32 s36, s51, s0
	s_cselect_b32 s35, s21, s54
	s_cselect_b32 s34, s52, s53
	v_lshl_add_u64 v[148:149], s[30:31], 0, v[140:141]
	s_add_i32 m0, s25, 0xc000
	ds_read_b128 v[172:175], v153
	ds_read_b128 v[176:179], v153 offset:1024
	ds_read_b128 v[180:183], v153 offset:2048
	ds_read_b128 v[184:187], v153 offset:3072
	ds_read_b128 v[188:191], v153 offset:4096
	ds_read_b128 v[192:195], v153 offset:5120
	ds_read_b128 v[196:199], v153 offset:6144
	ds_read_b128 v[200:203], v153 offset:7168
	global_load_lds_dwordx4 v[148:149], off
	v_lshl_add_u64 v[148:149], s[30:31], 0, v[138:139]
	s_add_i32 m0, s25, 0xe000
	s_nop 0
	global_load_lds_dwordx4 v[148:149], off
	s_waitcnt lgkmcnt(8)
	s_waitcnt vmcnt(10)
	s_barrier
	s_waitcnt lgkmcnt(0)
	s_waitcnt lgkmcnt(0)
	v_mfma_f32_16x16x32_bf16 v[126:129], v[156:159], v[172:175], v[126:129]
	v_mfma_f32_16x16x32_bf16 v[122:125], v[164:167], v[172:175], v[122:125]
	v_mfma_f32_16x16x32_bf16 v[118:121], v[156:159], v[180:183], v[118:121]
	v_mfma_f32_16x16x32_bf16 v[110:113], v[164:167], v[180:183], v[110:113]
	v_mfma_f32_16x16x32_bf16 v[102:105], v[156:159], v[188:191], v[102:105]
	v_mfma_f32_16x16x32_bf16 v[94:97], v[164:167], v[188:191], v[94:97]
	v_mfma_f32_16x16x32_bf16 v[86:89], v[156:159], v[196:199], v[86:89]
	v_mfma_f32_16x16x32_bf16 v[78:81], v[164:167], v[196:199], v[78:81]
	v_mfma_f32_16x16x32_bf16 v[126:129], v[160:163], v[176:179], v[126:129]
	v_mfma_f32_16x16x32_bf16 v[122:125], v[168:171], v[176:179], v[122:125]
	v_mfma_f32_16x16x32_bf16 v[118:121], v[160:163], v[184:187], v[118:121]
	v_mfma_f32_16x16x32_bf16 v[110:113], v[168:171], v[184:187], v[110:113]
	v_mfma_f32_16x16x32_bf16 v[102:105], v[160:163], v[192:195], v[102:105]
	v_mfma_f32_16x16x32_bf16 v[94:97], v[168:171], v[192:195], v[94:97]
	v_mfma_f32_16x16x32_bf16 v[86:89], v[160:163], v[200:203], v[86:89]
	v_mfma_f32_16x16x32_bf16 v[78:81], v[168:171], v[200:203], v[78:81]
	s_barrier
	s_add_i32 s0, s47, s11
	v_lshl_add_u64 v[148:149], s[34:35], 0, v[134:135]
	s_mov_b32 m0, s0
	ds_read_b128 v[204:207], v154
	ds_read_b128 v[208:211], v154 offset:1024
	ds_read_b128 v[212:215], v154 offset:2048
	ds_read_b128 v[216:219], v154 offset:3072
	global_load_lds_dwordx4 v[148:149], off
	v_lshl_add_u64 v[220:221], s[34:35], 0, v[130:131]
	s_add_i32 m0, s0, 0x2000
	s_nop 0
	global_load_lds_dwordx4 v[220:221], off
	s_waitcnt vmcnt(10)
	s_barrier
	s_waitcnt lgkmcnt(0)
	s_waitcnt lgkmcnt(0)
	v_mfma_f32_16x16x32_bf16 v[114:117], v[204:207], v[172:175], v[114:117]
	v_mfma_f32_16x16x32_bf16 v[106:109], v[212:215], v[172:175], v[106:109]
	v_mfma_f32_16x16x32_bf16 v[98:101], v[204:207], v[180:183], v[98:101]
	v_mfma_f32_16x16x32_bf16 v[90:93], v[212:215], v[180:183], v[90:93]
	v_mfma_f32_16x16x32_bf16 v[82:85], v[204:207], v[188:191], v[82:85]
	v_mfma_f32_16x16x32_bf16 v[74:77], v[212:215], v[188:191], v[74:77]
	v_mfma_f32_16x16x32_bf16 v[70:73], v[204:207], v[196:199], v[70:73]
	v_mfma_f32_16x16x32_bf16 v[66:69], v[212:215], v[196:199], v[66:69]
	v_mfma_f32_16x16x32_bf16 v[114:117], v[208:211], v[176:179], v[114:117]
	v_mfma_f32_16x16x32_bf16 v[106:109], v[216:219], v[176:179], v[106:109]
	v_mfma_f32_16x16x32_bf16 v[98:101], v[208:211], v[184:187], v[98:101]
	v_mfma_f32_16x16x32_bf16 v[90:93], v[216:219], v[184:187], v[90:93]
	v_mfma_f32_16x16x32_bf16 v[82:85], v[208:211], v[192:195], v[82:85]
	v_mfma_f32_16x16x32_bf16 v[74:77], v[216:219], v[192:195], v[74:77]
	v_mfma_f32_16x16x32_bf16 v[70:73], v[208:211], v[200:203], v[70:73]
	v_mfma_f32_16x16x32_bf16 v[66:69], v[216:219], v[200:203], v[66:69]
	s_mov_b32 m0, s25
	v_lshl_add_u64 v[222:223], s[36:37], 0, v[136:137]
	s_barrier
	ds_read_b128 v[172:175], v153 offset:16384
	ds_read_b128 v[176:179], v153 offset:17408
	ds_read_b128 v[180:183], v153 offset:18432
	ds_read_b128 v[184:187], v153 offset:19456
	ds_read_b128 v[188:191], v153 offset:20480
	ds_read_b128 v[192:195], v153 offset:21504
	ds_read_b128 v[196:199], v153 offset:22528
	ds_read_b128 v[200:203], v153 offset:23552
	global_load_lds_dwordx4 v[222:223], off
	v_lshl_add_u64 v[224:225], s[36:37], 0, v[132:133]
	s_mov_b32 m0, s39
	s_nop 0
	global_load_lds_dwordx4 v[224:225], off
	s_waitcnt vmcnt(10)
	s_barrier
	s_waitcnt lgkmcnt(0)
	s_waitcnt lgkmcnt(0)
	v_mfma_f32_16x16x32_bf16 v[62:65], v[156:159], v[172:175], v[62:65]
	v_mfma_f32_16x16x32_bf16 v[58:61], v[164:167], v[172:175], v[58:61]
	v_mfma_f32_16x16x32_bf16 v[54:57], v[156:159], v[180:183], v[54:57]
	v_mfma_f32_16x16x32_bf16 v[46:49], v[164:167], v[180:183], v[46:49]
	v_mfma_f32_16x16x32_bf16 v[38:41], v[156:159], v[188:191], v[38:41]
	v_mfma_f32_16x16x32_bf16 v[30:33], v[164:167], v[188:191], v[30:33]
	v_mfma_f32_16x16x32_bf16 v[22:25], v[156:159], v[196:199], v[22:25]
	v_mfma_f32_16x16x32_bf16 v[14:17], v[164:167], v[196:199], v[14:17]
	v_mfma_f32_16x16x32_bf16 v[62:65], v[160:163], v[176:179], v[62:65]
	v_mfma_f32_16x16x32_bf16 v[58:61], v[168:171], v[176:179], v[58:61]
	v_mfma_f32_16x16x32_bf16 v[54:57], v[160:163], v[184:187], v[54:57]
	v_mfma_f32_16x16x32_bf16 v[46:49], v[168:171], v[184:187], v[46:49]
	v_mfma_f32_16x16x32_bf16 v[38:41], v[160:163], v[192:195], v[38:41]
	v_mfma_f32_16x16x32_bf16 v[30:33], v[168:171], v[192:195], v[30:33]
	v_mfma_f32_16x16x32_bf16 v[22:25], v[160:163], v[200:203], v[22:25]
	v_mfma_f32_16x16x32_bf16 v[14:17], v[168:171], v[200:203], v[14:17]
	s_barrier
	s_add_u32 s0, s34, 0x40000
	s_addc_u32 s1, s35, 0
	s_add_i32 s56, s48, s11
	v_lshl_add_u64 v[156:157], s[0:1], 0, v[134:135]
	s_mov_b32 m0, s56
	s_nop 0
	global_load_lds_dwordx4 v[156:157], off
	v_lshl_add_u64 v[156:157], s[0:1], 0, v[130:131]
	s_add_i32 m0, s56, 0x2000
	s_nop 0
	global_load_lds_dwordx4 v[156:157], off
	s_waitcnt vmcnt(10)
	s_barrier
	v_mfma_f32_16x16x32_bf16 v[50:53], v[204:207], v[172:175], v[50:53]
	v_mfma_f32_16x16x32_bf16 v[42:45], v[212:215], v[172:175], v[42:45]
	v_mfma_f32_16x16x32_bf16 v[34:37], v[204:207], v[180:183], v[34:37]
	v_mfma_f32_16x16x32_bf16 v[26:29], v[212:215], v[180:183], v[26:29]
	v_mfma_f32_16x16x32_bf16 v[18:21], v[204:207], v[188:191], v[18:21]
	v_mfma_f32_16x16x32_bf16 v[10:13], v[212:215], v[188:191], v[10:13]
	v_mfma_f32_16x16x32_bf16 v[6:9], v[204:207], v[196:199], v[6:9]
	v_mfma_f32_16x16x32_bf16 v[2:5], v[212:215], v[196:199], v[2:5]
	v_mfma_f32_16x16x32_bf16 v[50:53], v[208:211], v[176:179], v[50:53]
	v_mfma_f32_16x16x32_bf16 v[42:45], v[216:219], v[176:179], v[42:45]
	v_mfma_f32_16x16x32_bf16 v[34:37], v[208:211], v[184:187], v[34:37]
	v_mfma_f32_16x16x32_bf16 v[26:29], v[216:219], v[184:187], v[26:29]
	v_mfma_f32_16x16x32_bf16 v[18:21], v[208:211], v[192:195], v[18:21]
	v_mfma_f32_16x16x32_bf16 v[10:13], v[216:219], v[192:195], v[10:13]
	v_mfma_f32_16x16x32_bf16 v[6:9], v[208:211], v[200:203], v[6:9]
	v_mfma_f32_16x16x32_bf16 v[2:5], v[216:219], v[200:203], v[2:5]
	s_add_i32 s56, 0, 0x18000
	v_add_u32_e32 v146, s56, v151
	s_barrier
	ds_read_b128 v[156:159], v146
	ds_read_b128 v[160:163], v146 offset:1024
	ds_read_b128 v[164:167], v146 offset:2048
	ds_read_b128 v[168:171], v146 offset:3072
	s_add_u32 s0, s36, 0x40000
	s_addc_u32 s1, s37, 0
	s_mov_b32 m0, s40
	v_lshl_add_u64 v[204:205], s[0:1], 0, v[136:137]
	ds_read_b128 v[172:175], v153 offset:32768
	ds_read_b128 v[176:179], v153 offset:33792
	ds_read_b128 v[180:183], v153 offset:34816
	ds_read_b128 v[184:187], v153 offset:35840
	ds_read_b128 v[188:191], v153 offset:36864
	ds_read_b128 v[192:195], v153 offset:37888
	ds_read_b128 v[196:199], v153 offset:38912
	ds_read_b128 v[200:203], v153 offset:39936
	global_load_lds_dwordx4 v[204:205], off
	v_lshl_add_u64 v[204:205], s[0:1], 0, v[132:133]
	s_mov_b32 m0, s41
	s_nop 0
	global_load_lds_dwordx4 v[204:205], off
	s_waitcnt lgkmcnt(8)
	s_waitcnt vmcnt(10)
	s_barrier
	s_waitcnt lgkmcnt(0)
	s_waitcnt lgkmcnt(0)
	v_mfma_f32_16x16x32_bf16 v[126:129], v[156:159], v[172:175], v[126:129]
	v_mfma_f32_16x16x32_bf16 v[122:125], v[164:167], v[172:175], v[122:125]
	v_mfma_f32_16x16x32_bf16 v[118:121], v[156:159], v[180:183], v[118:121]
	v_mfma_f32_16x16x32_bf16 v[110:113], v[164:167], v[180:183], v[110:113]
	v_mfma_f32_16x16x32_bf16 v[102:105], v[156:159], v[188:191], v[102:105]
	v_mfma_f32_16x16x32_bf16 v[94:97], v[164:167], v[188:191], v[94:97]
	v_mfma_f32_16x16x32_bf16 v[86:89], v[156:159], v[196:199], v[86:89]
	v_mfma_f32_16x16x32_bf16 v[78:81], v[164:167], v[196:199], v[78:81]
	v_mfma_f32_16x16x32_bf16 v[126:129], v[160:163], v[176:179], v[126:129]
	v_mfma_f32_16x16x32_bf16 v[122:125], v[168:171], v[176:179], v[122:125]
	v_mfma_f32_16x16x32_bf16 v[118:121], v[160:163], v[184:187], v[118:121]
	v_mfma_f32_16x16x32_bf16 v[110:113], v[168:171], v[184:187], v[110:113]
	v_mfma_f32_16x16x32_bf16 v[102:105], v[160:163], v[192:195], v[102:105]
	v_mfma_f32_16x16x32_bf16 v[94:97], v[168:171], v[192:195], v[94:97]
	v_mfma_f32_16x16x32_bf16 v[86:89], v[160:163], v[200:203], v[86:89]
	v_mfma_f32_16x16x32_bf16 v[78:81], v[168:171], v[200:203], v[78:81]
	s_barrier
	s_add_i32 s36, 0, 0x1c000
	s_add_i32 s0, s56, s11
	v_add_u32_e32 v146, s36, v151
	v_lshl_add_u64 v[148:149], v[148:149], 0, s[16:17]
	s_mov_b32 m0, s0
	ds_read_b128 v[204:207], v146
	ds_read_b128 v[208:211], v146 offset:1024
	ds_read_b128 v[212:215], v146 offset:2048
	ds_read_b128 v[216:219], v146 offset:3072
	global_load_lds_dwordx4 v[148:149], off
	v_lshl_add_u64 v[148:149], v[220:221], 0, s[16:17]
	s_add_i32 m0, s0, 0x2000
	s_nop 0
	global_load_lds_dwordx4 v[148:149], off
	s_waitcnt vmcnt(10)
	s_barrier
	s_waitcnt lgkmcnt(0)
	s_waitcnt lgkmcnt(0)
	v_mfma_f32_16x16x32_bf16 v[114:117], v[204:207], v[172:175], v[114:117]
	v_mfma_f32_16x16x32_bf16 v[106:109], v[212:215], v[172:175], v[106:109]
	v_mfma_f32_16x16x32_bf16 v[98:101], v[204:207], v[180:183], v[98:101]
	v_mfma_f32_16x16x32_bf16 v[90:93], v[212:215], v[180:183], v[90:93]
	v_mfma_f32_16x16x32_bf16 v[82:85], v[204:207], v[188:191], v[82:85]
	v_mfma_f32_16x16x32_bf16 v[74:77], v[212:215], v[188:191], v[74:77]
	v_mfma_f32_16x16x32_bf16 v[70:73], v[204:207], v[196:199], v[70:73]
	v_mfma_f32_16x16x32_bf16 v[66:69], v[212:215], v[196:199], v[66:69]
	v_mfma_f32_16x16x32_bf16 v[114:117], v[208:211], v[176:179], v[114:117]
	v_mfma_f32_16x16x32_bf16 v[106:109], v[216:219], v[176:179], v[106:109]
	v_mfma_f32_16x16x32_bf16 v[98:101], v[208:211], v[184:187], v[98:101]
	v_mfma_f32_16x16x32_bf16 v[90:93], v[216:219], v[184:187], v[90:93]
	v_mfma_f32_16x16x32_bf16 v[82:85], v[208:211], v[192:195], v[82:85]
	v_mfma_f32_16x16x32_bf16 v[74:77], v[216:219], v[192:195], v[74:77]
	v_mfma_f32_16x16x32_bf16 v[70:73], v[208:211], v[200:203], v[70:73]
	v_mfma_f32_16x16x32_bf16 v[66:69], v[216:219], v[200:203], v[66:69]
	s_mov_b32 m0, s45
	v_lshl_add_u64 v[148:149], v[222:223], 0, s[16:17]
	s_barrier
	ds_read_b128 v[172:175], v153 offset:49152
	ds_read_b128 v[176:179], v153 offset:50176
	ds_read_b128 v[180:183], v153 offset:51200
	ds_read_b128 v[184:187], v153 offset:52224
	ds_read_b128 v[188:191], v153 offset:53248
	ds_read_b128 v[192:195], v153 offset:54272
	ds_read_b128 v[196:199], v153 offset:55296
	ds_read_b128 v[200:203], v153 offset:56320
	global_load_lds_dwordx4 v[148:149], off
	v_lshl_add_u64 v[148:149], v[224:225], 0, s[16:17]
	s_mov_b32 m0, s46
	s_nop 0
	global_load_lds_dwordx4 v[148:149], off
	s_waitcnt vmcnt(10)
	s_barrier
	s_waitcnt lgkmcnt(0)
	s_waitcnt lgkmcnt(0)
	v_mfma_f32_16x16x32_bf16 v[62:65], v[156:159], v[172:175], v[62:65]
	v_mfma_f32_16x16x32_bf16 v[58:61], v[164:167], v[172:175], v[58:61]
	v_mfma_f32_16x16x32_bf16 v[54:57], v[156:159], v[180:183], v[54:57]
	v_mfma_f32_16x16x32_bf16 v[46:49], v[164:167], v[180:183], v[46:49]
	v_mfma_f32_16x16x32_bf16 v[38:41], v[156:159], v[188:191], v[38:41]
	v_mfma_f32_16x16x32_bf16 v[30:33], v[164:167], v[188:191], v[30:33]
	v_mfma_f32_16x16x32_bf16 v[22:25], v[156:159], v[196:199], v[22:25]
	v_mfma_f32_16x16x32_bf16 v[14:17], v[164:167], v[196:199], v[14:17]
	v_mfma_f32_16x16x32_bf16 v[62:65], v[160:163], v[176:179], v[62:65]
	v_mfma_f32_16x16x32_bf16 v[58:61], v[168:171], v[176:179], v[58:61]
	v_mfma_f32_16x16x32_bf16 v[54:57], v[160:163], v[184:187], v[54:57]
	v_mfma_f32_16x16x32_bf16 v[46:49], v[168:171], v[184:187], v[46:49]
	v_mfma_f32_16x16x32_bf16 v[38:41], v[160:163], v[192:195], v[38:41]
	v_mfma_f32_16x16x32_bf16 v[30:33], v[168:171], v[192:195], v[30:33]
	v_mfma_f32_16x16x32_bf16 v[22:25], v[160:163], v[200:203], v[22:25]
	v_mfma_f32_16x16x32_bf16 v[14:17], v[168:171], v[200:203], v[14:17]
	s_barrier
	s_add_u32 s0, s34, 0x40080
	s_addc_u32 s1, s35, 0
	s_add_i32 s34, s36, s11
	v_lshl_add_u64 v[148:149], s[0:1], 0, v[134:135]
	s_mov_b32 m0, s34
	s_nop 0
	global_load_lds_dwordx4 v[148:149], off
	v_lshl_add_u64 v[148:149], s[0:1], 0, v[130:131]
	s_add_i32 m0, s34, 0x2000
	s_nop 0
	global_load_lds_dwordx4 v[148:149], off
	s_waitcnt vmcnt(10)
	s_barrier
	v_mfma_f32_16x16x32_bf16 v[50:53], v[204:207], v[172:175], v[50:53]
	v_mfma_f32_16x16x32_bf16 v[42:45], v[212:215], v[172:175], v[42:45]
	v_mfma_f32_16x16x32_bf16 v[34:37], v[204:207], v[180:183], v[34:37]
	v_mfma_f32_16x16x32_bf16 v[26:29], v[212:215], v[180:183], v[26:29]
	v_mfma_f32_16x16x32_bf16 v[18:21], v[204:207], v[188:191], v[18:21]
	v_mfma_f32_16x16x32_bf16 v[10:13], v[212:215], v[188:191], v[10:13]
	v_mfma_f32_16x16x32_bf16 v[6:9], v[204:207], v[196:199], v[6:9]
	v_mfma_f32_16x16x32_bf16 v[2:5], v[212:215], v[196:199], v[2:5]
	v_mfma_f32_16x16x32_bf16 v[50:53], v[208:211], v[176:179], v[50:53]
	v_mfma_f32_16x16x32_bf16 v[42:45], v[216:219], v[176:179], v[42:45]
	v_mfma_f32_16x16x32_bf16 v[34:37], v[208:211], v[184:187], v[34:37]
	v_mfma_f32_16x16x32_bf16 v[26:29], v[216:219], v[184:187], v[26:29]
	v_mfma_f32_16x16x32_bf16 v[18:21], v[208:211], v[192:195], v[18:21]
	v_mfma_f32_16x16x32_bf16 v[10:13], v[216:219], v[192:195], v[10:13]
	v_mfma_f32_16x16x32_bf16 v[6:9], v[208:211], v[200:203], v[6:9]
	v_mfma_f32_16x16x32_bf16 v[2:5], v[216:219], v[200:203], v[2:5]
	s_add_i32 s55, s55, 2
	s_add_u32 s53, s53, 0x100
	s_addc_u32 s54, s54, 0
	s_add_u32 s30, s30, 0x100
	s_addc_u32 s31, s31, 0
	s_cmp_gt_u32 s55, 13
	s_barrier
	s_cbranch_scc0 .LBB0_895
	v_mov_b32_e32 v156, v147
	v_mov_b32_e32 v146, v150
	s_cmp_gt_i32 s50, 11
	s_mov_b64 s[30:31], -1
	s_cbranch_scc0 .LBB0_900
	s_cmp_eq_u32 s50, 12
	s_cselect_b64 s[0:1], -1, 0
	s_and_b64 s[0:1], s[0:1], s[18:19]
	v_cmp_gt_i32_e32 vcc, 4, v146
	s_and_b64 s[0:1], s[0:1], vcc
	s_and_saveexec_b64 s[30:31], s[0:1]
	s_cbranch_execz .LBB0_899
	s_lshl_b32 s0, s24, 8
	s_add_i32 s0, s0, s43
	v_add_u32_e32 v157, s0, v156
	v_mov_b32_e32 v158, v157
	v_lshlrev_b32_e32 v148, 3, v146
	v_ashrrev_i32_e32 v149, 31, v148
	v_ashrrev_i32_e32 v159, 31, v158
	v_lshlrev_b64 v[158:159], 7, v[158:159]
	v_lshl_add_u64 v[158:159], s[14:15], 0, v[158:159]
	v_lshlrev_b64 v[148:149], 2, v[148:149]
	v_lshl_add_u64 v[162:163], v[158:159], 0, v[148:149]
	v_pk_add_f32 v[160:161], v[128:129], 0 op_sel_hi:[1,0]
	v_pk_add_f32 v[158:159], v[126:127], 0 op_sel_hi:[1,0]
	global_store_dwordx4 v[162:163], v[158:161], off
	s_nop 1
	v_pk_add_f32 v[160:161], v[124:125], 0 op_sel_hi:[1,0]
	v_pk_add_f32 v[158:159], v[122:123], 0 op_sel_hi:[1,0]
	global_store_dwordx4 v[162:163], v[158:161], off offset:16
	s_nop 1
	v_add_u32_e32 v158, 16, v157
	v_pk_add_f32 v[160:161], v[120:121], 0 op_sel_hi:[1,0]
	v_ashrrev_i32_e32 v159, 31, v158
	v_lshlrev_b64 v[158:159], 7, v[158:159]
	v_lshl_add_u64 v[158:159], s[14:15], 0, v[158:159]
	v_lshl_add_u64 v[162:163], v[158:159], 0, v[148:149]
	v_pk_add_f32 v[158:159], v[118:119], 0 op_sel_hi:[1,0]
	global_store_dwordx4 v[162:163], v[158:161], off
	s_nop 1
	v_pk_add_f32 v[160:161], v[112:113], 0 op_sel_hi:[1,0]
	v_pk_add_f32 v[158:159], v[110:111], 0 op_sel_hi:[1,0]
	global_store_dwordx4 v[162:163], v[158:161], off offset:16
	s_nop 1
	v_add_u32_e32 v158, 32, v157
	v_pk_add_f32 v[160:161], v[104:105], 0 op_sel_hi:[1,0]
	v_ashrrev_i32_e32 v159, 31, v158
	v_lshlrev_b64 v[158:159], 7, v[158:159]
	v_lshl_add_u64 v[158:159], s[14:15], 0, v[158:159]
	v_lshl_add_u64 v[162:163], v[158:159], 0, v[148:149]
	v_pk_add_f32 v[158:159], v[102:103], 0 op_sel_hi:[1,0]
	global_store_dwordx4 v[162:163], v[158:161], off
	s_nop 1
	v_pk_add_f32 v[160:161], v[96:97], 0 op_sel_hi:[1,0]
	v_pk_add_f32 v[158:159], v[94:95], 0 op_sel_hi:[1,0]
	global_store_dwordx4 v[162:163], v[158:161], off offset:16
	s_nop 1
	v_add_u32_e32 v158, 48, v157
	v_pk_add_f32 v[160:161], v[88:89], 0 op_sel_hi:[1,0]
	v_ashrrev_i32_e32 v159, 31, v158
	v_lshlrev_b64 v[158:159], 7, v[158:159]
	v_lshl_add_u64 v[158:159], s[14:15], 0, v[158:159]
	v_lshl_add_u64 v[162:163], v[158:159], 0, v[148:149]
	v_pk_add_f32 v[158:159], v[86:87], 0 op_sel_hi:[1,0]
	global_store_dwordx4 v[162:163], v[158:161], off
	s_nop 1
	v_pk_add_f32 v[160:161], v[80:81], 0 op_sel_hi:[1,0]
	v_pk_add_f32 v[158:159], v[78:79], 0 op_sel_hi:[1,0]
	global_store_dwordx4 v[162:163], v[158:161], off offset:16
	s_nop 1
	v_add_u32_e32 v158, 0x80, v157
	v_pk_add_f32 v[160:161], v[64:65], 0 op_sel_hi:[1,0]
	v_ashrrev_i32_e32 v159, 31, v158
	v_lshlrev_b64 v[158:159], 7, v[158:159]
	v_lshl_add_u64 v[158:159], s[14:15], 0, v[158:159]
	v_lshl_add_u64 v[162:163], v[158:159], 0, v[148:149]
	v_pk_add_f32 v[158:159], v[62:63], 0 op_sel_hi:[1,0]
	global_store_dwordx4 v[162:163], v[158:161], off
	s_nop 1
	v_pk_add_f32 v[160:161], v[60:61], 0 op_sel_hi:[1,0]
	v_pk_add_f32 v[158:159], v[58:59], 0 op_sel_hi:[1,0]
	global_store_dwordx4 v[162:163], v[158:161], off offset:16
	s_nop 1
	v_add_u32_e32 v158, 0x90, v157
	v_pk_add_f32 v[160:161], v[56:57], 0 op_sel_hi:[1,0]
	v_ashrrev_i32_e32 v159, 31, v158
	v_lshlrev_b64 v[158:159], 7, v[158:159]
	v_lshl_add_u64 v[158:159], s[14:15], 0, v[158:159]
	v_lshl_add_u64 v[162:163], v[158:159], 0, v[148:149]
	v_pk_add_f32 v[158:159], v[54:55], 0 op_sel_hi:[1,0]
	global_store_dwordx4 v[162:163], v[158:161], off
	s_nop 1
	v_pk_add_f32 v[160:161], v[48:49], 0 op_sel_hi:[1,0]
	v_pk_add_f32 v[158:159], v[46:47], 0 op_sel_hi:[1,0]
	global_store_dwordx4 v[162:163], v[158:161], off offset:16
	s_nop 1
	v_add_u32_e32 v158, 0xa0, v157
	v_pk_add_f32 v[160:161], v[40:41], 0 op_sel_hi:[1,0]
	v_ashrrev_i32_e32 v159, 31, v158
	v_lshlrev_b64 v[158:159], 7, v[158:159]
	v_lshl_add_u64 v[158:159], s[14:15], 0, v[158:159]
	v_lshl_add_u64 v[162:163], v[158:159], 0, v[148:149]
	v_pk_add_f32 v[158:159], v[38:39], 0 op_sel_hi:[1,0]
	global_store_dwordx4 v[162:163], v[158:161], off
	s_nop 1
	v_pk_add_f32 v[160:161], v[32:33], 0 op_sel_hi:[1,0]
	v_pk_add_f32 v[158:159], v[30:31], 0 op_sel_hi:[1,0]
	global_store_dwordx4 v[162:163], v[158:161], off offset:16
	s_nop 1
	v_add_u32_e32 v158, 0xb0, v157
	v_pk_add_f32 v[160:161], v[24:25], 0 op_sel_hi:[1,0]
	v_ashrrev_i32_e32 v159, 31, v158
	v_lshlrev_b64 v[158:159], 7, v[158:159]
	v_lshl_add_u64 v[158:159], s[14:15], 0, v[158:159]
	v_lshl_add_u64 v[148:149], v[158:159], 0, v[148:149]
	v_pk_add_f32 v[158:159], v[22:23], 0 op_sel_hi:[1,0]
	global_store_dwordx4 v[148:149], v[158:161], off
	s_nop 1
	v_pk_add_f32 v[160:161], v[16:17], 0 op_sel_hi:[1,0]
	v_pk_add_f32 v[158:159], v[14:15], 0 op_sel_hi:[1,0]
	global_store_dwordx4 v[148:149], v[158:161], off offset:16

.LBB0_900:
	s_andn2_b64 vcc, exec, s[30:31]
	s_cbranch_vccnz .LBB0_891
	s_lshl_b32 s0, s50, 8
	s_or_b32 s0, s0, s44
	s_cmp_lt_i32 s50, 2
	v_lshl_add_u32 v148, v146, 3, s0
	s_cselect_b64 vcc, -1, 0
	s_lshl_b32 s0, s24, 8
	s_add_i32 s0, s0, s43
	v_add_u32_e32 v160, s0, v156
	v_cndmask_b32_e32 v146, 1.0, v155, vcc
	v_ashrrev_i32_e32 v149, 31, v148
	v_mov_b32_e32 v156, v160
	v_lshl_add_u64 v[148:149], v[148:149], 1, s[12:13]
	v_pk_mul_f32 v[128:129], v[146:147], v[128:129] op_sel_hi:[0,1]
	v_pk_mul_f32 v[126:127], v[146:147], v[126:127] op_sel_hi:[0,1]
	v_pk_mul_f32 v[158:159], v[146:147], v[124:125] op_sel_hi:[0,1]
	v_pk_mul_f32 v[124:125], v[146:147], v[122:123] op_sel_hi:[0,1]
	v_mad_i64_i32 v[156:157], s[0:1], v156, s49, v[148:149]
	v_cvt_pk_bf16_f32 v122, v126, v127
	v_cvt_pk_bf16_f32 v123, v128, v129
	v_cvt_pk_bf16_f32 v124, v124, v125
	v_cvt_pk_bf16_f32 v125, v158, v159
	global_store_dwordx4 v[156:157], v[122:125], off
	v_pk_mul_f32 v[116:117], v[146:147], v[116:117] op_sel_hi:[0,1]
	v_pk_mul_f32 v[114:115], v[146:147], v[114:115] op_sel_hi:[0,1]
	v_pk_mul_f32 v[122:123], v[146:147], v[108:109] op_sel_hi:[0,1]
	v_pk_mul_f32 v[108:109], v[146:147], v[106:107] op_sel_hi:[0,1]
	v_cvt_pk_bf16_f32 v106, v114, v115
	v_cvt_pk_bf16_f32 v107, v116, v117
	v_cvt_pk_bf16_f32 v108, v108, v109
	v_cvt_pk_bf16_f32 v109, v122, v123
	global_store_dwordx4 v[156:157], v[106:109], off offset:256
	v_pk_mul_f32 v[112:113], v[146:147], v[112:113] op_sel_hi:[0,1]
	v_pk_mul_f32 v[110:111], v[146:147], v[110:111] op_sel_hi:[0,1]
	v_add_u32_e32 v106, 16, v160
	v_pk_mul_f32 v[108:109], v[146:147], v[120:121] op_sel_hi:[0,1]
	v_mad_i64_i32 v[114:115], s[0:1], v106, s49, v[148:149]
	v_pk_mul_f32 v[106:107], v[146:147], v[118:119] op_sel_hi:[0,1]
	v_cvt_pk_bf16_f32 v106, v106, v107
	v_cvt_pk_bf16_f32 v107, v108, v109
	v_cvt_pk_bf16_f32 v108, v110, v111
	v_cvt_pk_bf16_f32 v109, v112, v113
	global_store_dwordx4 v[114:115], v[106:109], off
	v_pk_mul_f32 v[100:101], v[146:147], v[100:101] op_sel_hi:[0,1]
	v_pk_mul_f32 v[98:99], v[146:147], v[98:99] op_sel_hi:[0,1]
	v_pk_mul_f32 v[106:107], v[146:147], v[92:93] op_sel_hi:[0,1]
	v_pk_mul_f32 v[92:93], v[146:147], v[90:91] op_sel_hi:[0,1]
	v_cvt_pk_bf16_f32 v90, v98, v99
	v_cvt_pk_bf16_f32 v91, v100, v101
	v_cvt_pk_bf16_f32 v92, v92, v93
	v_cvt_pk_bf16_f32 v93, v106, v107
	global_store_dwordx4 v[114:115], v[90:93], off offset:256
	v_pk_mul_f32 v[96:97], v[146:147], v[96:97] op_sel_hi:[0,1]
	v_pk_mul_f32 v[94:95], v[146:147], v[94:95] op_sel_hi:[0,1]
	v_add_u32_e32 v90, 32, v160
	v_pk_mul_f32 v[92:93], v[146:147], v[104:105] op_sel_hi:[0,1]
	v_mad_i64_i32 v[98:99], s[0:1], v90, s49, v[148:149]
	v_pk_mul_f32 v[90:91], v[146:147], v[102:103] op_sel_hi:[0,1]
	v_cvt_pk_bf16_f32 v90, v90, v91
	v_cvt_pk_bf16_f32 v91, v92, v93
	v_cvt_pk_bf16_f32 v92, v94, v95
	v_cvt_pk_bf16_f32 v93, v96, v97
	global_store_dwordx4 v[98:99], v[90:93], off
	v_pk_mul_f32 v[84:85], v[146:147], v[84:85] op_sel_hi:[0,1]
	v_pk_mul_f32 v[82:83], v[146:147], v[82:83] op_sel_hi:[0,1]
	v_pk_mul_f32 v[90:91], v[146:147], v[76:77] op_sel_hi:[0,1]
	v_pk_mul_f32 v[76:77], v[146:147], v[74:75] op_sel_hi:[0,1]
	v_cvt_pk_bf16_f32 v74, v82, v83
	v_cvt_pk_bf16_f32 v75, v84, v85
	v_cvt_pk_bf16_f32 v76, v76, v77
	v_cvt_pk_bf16_f32 v77, v90, v91
	global_store_dwordx4 v[98:99], v[74:77], off offset:256
	v_pk_mul_f32 v[80:81], v[146:147], v[80:81] op_sel_hi:[0,1]
	v_pk_mul_f32 v[78:79], v[146:147], v[78:79] op_sel_hi:[0,1]
	v_add_u32_e32 v74, 48, v160
	v_pk_mul_f32 v[76:77], v[146:147], v[88:89] op_sel_hi:[0,1]
	v_mad_i64_i32 v[82:83], s[0:1], v74, s49, v[148:149]
	v_pk_mul_f32 v[74:75], v[146:147], v[86:87] op_sel_hi:[0,1]
	v_cvt_pk_bf16_f32 v74, v74, v75
	v_cvt_pk_bf16_f32 v75, v76, v77
	v_cvt_pk_bf16_f32 v76, v78, v79
	v_cvt_pk_bf16_f32 v77, v80, v81
	global_store_dwordx4 v[82:83], v[74:77], off
	v_pk_mul_f32 v[72:73], v[146:147], v[72:73] op_sel_hi:[0,1]
	v_pk_mul_f32 v[70:71], v[146:147], v[70:71] op_sel_hi:[0,1]
	v_pk_mul_f32 v[74:75], v[146:147], v[68:69] op_sel_hi:[0,1]
	v_pk_mul_f32 v[68:69], v[146:147], v[66:67] op_sel_hi:[0,1]
	v_cvt_pk_bf16_f32 v66, v70, v71
	v_cvt_pk_bf16_f32 v67, v72, v73
	v_cvt_pk_bf16_f32 v68, v68, v69
	v_cvt_pk_bf16_f32 v69, v74, v75
	global_store_dwordx4 v[82:83], v[66:69], off offset:256
	v_pk_mul_f32 v[64:65], v[146:147], v[64:65] op_sel_hi:[0,1]
	v_pk_mul_f32 v[62:63], v[146:147], v[62:63] op_sel_hi:[0,1]
	v_add_u32_e32 v66, 0x80, v160
	v_pk_mul_f32 v[68:69], v[146:147], v[60:61] op_sel_hi:[0,1]
	v_pk_mul_f32 v[60:61], v[146:147], v[58:59] op_sel_hi:[0,1]
	v_mad_i64_i32 v[66:67], s[0:1], v66, s49, v[148:149]
	v_cvt_pk_bf16_f32 v58, v62, v63
	v_cvt_pk_bf16_f32 v59, v64, v65
	v_cvt_pk_bf16_f32 v60, v60, v61
	v_cvt_pk_bf16_f32 v61, v68, v69
	global_store_dwordx4 v[66:67], v[58:61], off
	v_pk_mul_f32 v[52:53], v[146:147], v[52:53] op_sel_hi:[0,1]
	v_pk_mul_f32 v[50:51], v[146:147], v[50:51] op_sel_hi:[0,1]
	v_pk_mul_f32 v[58:59], v[146:147], v[44:45] op_sel_hi:[0,1]
	v_pk_mul_f32 v[44:45], v[146:147], v[42:43] op_sel_hi:[0,1]
	v_cvt_pk_bf16_f32 v42, v50, v51
	v_cvt_pk_bf16_f32 v43, v52, v53
	v_cvt_pk_bf16_f32 v44, v44, v45
	v_cvt_pk_bf16_f32 v45, v58, v59
	global_store_dwordx4 v[66:67], v[42:45], off offset:256
	v_pk_mul_f32 v[48:49], v[146:147], v[48:49] op_sel_hi:[0,1]
	v_pk_mul_f32 v[46:47], v[146:147], v[46:47] op_sel_hi:[0,1]
	v_add_u32_e32 v42, 0x90, v160
	v_pk_mul_f32 v[44:45], v[146:147], v[56:57] op_sel_hi:[0,1]
	v_mad_i64_i32 v[50:51], s[0:1], v42, s49, v[148:149]
	v_pk_mul_f32 v[42:43], v[146:147], v[54:55] op_sel_hi:[0,1]
	v_cvt_pk_bf16_f32 v42, v42, v43
	v_cvt_pk_bf16_f32 v43, v44, v45
	v_cvt_pk_bf16_f32 v44, v46, v47
	v_cvt_pk_bf16_f32 v45, v48, v49
	global_store_dwordx4 v[50:51], v[42:45], off
	v_pk_mul_f32 v[36:37], v[146:147], v[36:37] op_sel_hi:[0,1]
	v_pk_mul_f32 v[34:35], v[146:147], v[34:35] op_sel_hi:[0,1]
	v_pk_mul_f32 v[42:43], v[146:147], v[28:29] op_sel_hi:[0,1]
	v_pk_mul_f32 v[28:29], v[146:147], v[26:27] op_sel_hi:[0,1]
	v_cvt_pk_bf16_f32 v26, v34, v35
	v_cvt_pk_bf16_f32 v27, v36, v37
	v_cvt_pk_bf16_f32 v28, v28, v29
	v_cvt_pk_bf16_f32 v29, v42, v43
	global_store_dwordx4 v[50:51], v[26:29], off offset:256
	v_pk_mul_f32 v[32:33], v[146:147], v[32:33] op_sel_hi:[0,1]
	v_pk_mul_f32 v[30:31], v[146:147], v[30:31] op_sel_hi:[0,1]
	v_add_u32_e32 v26, 0xa0, v160
	v_pk_mul_f32 v[28:29], v[146:147], v[40:41] op_sel_hi:[0,1]
	v_mad_i64_i32 v[34:35], s[0:1], v26, s49, v[148:149]
	v_pk_mul_f32 v[26:27], v[146:147], v[38:39] op_sel_hi:[0,1]
	v_cvt_pk_bf16_f32 v26, v26, v27
	v_cvt_pk_bf16_f32 v27, v28, v29
	v_cvt_pk_bf16_f32 v28, v30, v31
	v_cvt_pk_bf16_f32 v29, v32, v33
	global_store_dwordx4 v[34:35], v[26:29], off
	v_pk_mul_f32 v[20:21], v[146:147], v[20:21] op_sel_hi:[0,1]
	v_pk_mul_f32 v[18:19], v[146:147], v[18:19] op_sel_hi:[0,1]
	v_pk_mul_f32 v[26:27], v[146:147], v[12:13] op_sel_hi:[0,1]
	v_pk_mul_f32 v[12:13], v[146:147], v[10:11] op_sel_hi:[0,1]
	v_cvt_pk_bf16_f32 v10, v18, v19
	v_cvt_pk_bf16_f32 v11, v20, v21
	v_cvt_pk_bf16_f32 v12, v12, v13
	v_cvt_pk_bf16_f32 v13, v26, v27
	global_store_dwordx4 v[34:35], v[10:13], off offset:256
	v_pk_mul_f32 v[16:17], v[146:147], v[16:17] op_sel_hi:[0,1]
	v_pk_mul_f32 v[14:15], v[146:147], v[14:15] op_sel_hi:[0,1]
	v_add_u32_e32 v10, 0xb0, v160
	v_pk_mul_f32 v[12:13], v[146:147], v[24:25] op_sel_hi:[0,1]
	v_mad_i64_i32 v[18:19], s[0:1], v10, s49, v[148:149]
	v_pk_mul_f32 v[10:11], v[146:147], v[22:23] op_sel_hi:[0,1]
	v_cvt_pk_bf16_f32 v10, v10, v11
	v_cvt_pk_bf16_f32 v11, v12, v13
	v_cvt_pk_bf16_f32 v12, v14, v15
	v_cvt_pk_bf16_f32 v13, v16, v17
	global_store_dwordx4 v[18:19], v[10:13], off
	v_pk_mul_f32 v[8:9], v[146:147], v[8:9] op_sel_hi:[0,1]
	v_pk_mul_f32 v[6:7], v[146:147], v[6:7] op_sel_hi:[0,1]
	v_pk_mul_f32 v[10:11], v[146:147], v[4:5] op_sel_hi:[0,1]
	v_pk_mul_f32 v[4:5], v[146:147], v[2:3] op_sel_hi:[0,1]
	v_cvt_pk_bf16_f32 v2, v6, v7
	v_cvt_pk_bf16_f32 v3, v8, v9
	v_cvt_pk_bf16_f32 v4, v4, v5
	v_cvt_pk_bf16_f32 v5, v10, v11
	global_store_dwordx4 v[18:19], v[2:5], off offset:256
	s_branch .LBB0_891

.LBB0_974:
	v_mov_b32_e32 v66, v159
	s_waitcnt lgkmcnt(0)
	s_barrier
	s_add_i32 s50, 0, 0x10000
	v_ashrrev_i32_e32 v67, 5, v66
	v_lshlrev_b32_e32 v68, 10, v66
	v_and_b32_e32 v70, 0xfffff0, v67
	v_lshlrev_b32_e32 v71, 1, v67
	v_and_b32_e32 v69, 0x4000, v68
	v_lshlrev_b32_e32 v68, 3, v66
	v_and_or_b32 v70, v71, 8, v70
	v_lshrrev_b32_e32 v71, 1, v67
	v_and_b32_e32 v73, 3, v67
	v_lshrrev_b32_e32 v70, 1, v70
	v_bfe_u32 v72, v68, 5, 2
	v_and_or_b32 v71, v71, 4, v73
	v_or_b32_e32 v70, v70, v72
	v_lshlrev_b32_e32 v71, 6, v71
	v_lshlrev_b32_e32 v73, 4, v66
	v_lshlrev_b32_e32 v70, 9, v70
	v_and_b32_e32 v73, 48, v73
	v_add3_u32 v71, 0, v69, v71
	v_add3_u32 v69, v71, v70, v73
	s_waitcnt vmcnt(0)
	ds_write_b128 v69, v[96:99] offset:32768
	v_add_u32_e32 v69, 16, v67
	v_and_b32_e32 v70, 0xfffff0, v69
	v_lshlrev_b32_e32 v74, 1, v69
	v_and_or_b32 v70, v74, 8, v70
	v_lshrrev_b32_e32 v70, 1, v70
	v_or_b32_e32 v70, v70, v72
	v_lshlrev_b32_e32 v70, 9, v70
	v_add3_u32 v70, v71, v70, v73
	ds_write_b128 v70, v[100:103] offset:32768
	v_ashrrev_i32_e32 v70, 4, v66
	v_and_b32_e32 v71, 15, v66
	v_lshlrev_b32_e32 v72, 9, v70
	v_lshlrev_b32_e32 v73, 5, v71
	v_add3_u32 v76, s50, v72, v73
	v_add_u32_e32 v72, 0, v73
	v_add_u32_e32 v84, 0x14000, v72
	ds_read_b128 v[72:75], v76
	ds_read_b128 v[76:79], v76 offset:16
	ds_read_b128 v[80:83], v84
	ds_read_b128 v[140:143], v84 offset:16
	v_lshlrev_b32_e32 v84, 16, v88
	s_waitcnt lgkmcnt(3)
	v_mul_f32_e32 v72, 0x3fb8aa3b, v72
	v_exp_f32_e32 v72, v72
	v_mul_f32_e32 v73, 0x3fb8aa3b, v73
	v_mul_f32_e32 v74, 0x3fb8aa3b, v74
	v_mul_f32_e32 v75, 0x3fb8aa3b, v75
	s_waitcnt lgkmcnt(2)
	v_mul_f32_e32 v76, 0x3fb8aa3b, v76
	v_mul_f32_e32 v77, 0x3fb8aa3b, v77
	v_exp_f32_e32 v73, v73
	v_exp_f32_e32 v74, v74
	v_exp_f32_e32 v75, v75
	v_exp_f32_e32 v76, v76
	v_exp_f32_e32 v77, v77
	v_mul_f32_e32 v78, 0x3fb8aa3b, v78
	v_mul_f32_e32 v79, 0x3fb8aa3b, v79
	v_exp_f32_e32 v78, v78
	v_exp_f32_e32 v79, v79
	v_and_b32_e32 v144, 0xffff0000, v88
	v_lshlrev_b32_e32 v145, 16, v89
	v_and_b32_e32 v146, 0xffff0000, v89
	v_lshlrev_b32_e32 v147, 16, v90
	v_and_b32_e32 v148, 0xffff0000, v90
	v_rcp_f32_e32 v86, v72
	v_mul_f32_e32 v72, v72, v84
	s_waitcnt lgkmcnt(0)
	v_mul_f32_e32 v84, 0x3fb8aa3b, v140
	v_rcp_f32_e32 v87, v73
	v_mul_f32_e32 v73, v73, v144
	v_rcp_f32_e32 v144, v74
	v_mul_f32_e32 v74, v74, v145
	v_rcp_f32_e32 v145, v75
	v_mul_f32_e32 v75, v75, v146
	v_rcp_f32_e32 v146, v76
	v_mul_f32_e32 v76, v76, v147
	v_exp_f32_e32 v140, v84
	v_rcp_f32_e32 v147, v77
	v_mul_f32_e32 v77, v77, v148
	v_mul_f32_e32 v84, 0x3fb8aa3b, v141
	v_lshlrev_b32_e32 v149, 16, v91
	v_and_b32_e32 v150, 0xffff0000, v91
	v_mul_f32_e32 v80, 0x3fb8aa3b, v80
	v_mul_f32_e32 v81, 0x3fb8aa3b, v81
	v_exp_f32_e32 v141, v84
	v_mul_f32_e32 v84, 0x3fb8aa3b, v142
	v_cvt_pk_bf16_f32 v72, v72, v73
	v_cvt_pk_bf16_f32 v73, v74, v75
	v_cvt_pk_bf16_f32 v74, v76, v77
	v_lshlrev_b32_e32 v76, 8, v70
	v_lshlrev_b32_e32 v71, 4, v71
	v_and_b32_e32 v77, 0x70, v66
	v_exp_f32_e32 v80, v80
	v_exp_f32_e32 v81, v81
	v_rcp_f32_e32 v148, v78
	v_mul_f32_e32 v78, v78, v149
	v_exp_f32_e32 v142, v84
	v_rcp_f32_e32 v149, v79
	v_mul_f32_e32 v79, v79, v150
	v_mul_f32_e32 v84, 0x3fb8aa3b, v143
	v_bitop3_b32 v76, v71, v76, v77 bitop3:0xde
	v_exp_f32_e32 v143, v84
	v_cvt_pk_bf16_f32 v75, v78, v79
	v_add_u32_e32 v84, 0, v76
	v_mul_f32_e32 v82, 0x3fb8aa3b, v82
	v_mul_f32_e32 v83, 0x3fb8aa3b, v83
	ds_write_b128 v84, v[72:75]
	v_lshlrev_b32_e32 v72, 16, v92
	v_and_b32_e32 v73, 0xffff0000, v92
	v_exp_f32_e32 v82, v82
	v_exp_f32_e32 v83, v83
	v_pk_mul_f32 v[72:73], v[86:87], v[72:73]
	s_add_i32 s49, s20, -3
	v_pk_mul_f32 v[74:75], v[72:73], v[80:81]
	v_cvt_pk_bf16_f32 v72, v72, v73
	v_cvt_pk_bf16_f32 v76, v74, v75
	v_lshlrev_b32_e32 v74, 16, v93
	v_and_b32_e32 v75, 0xffff0000, v93
	v_pk_mul_f32 v[74:75], v[144:145], v[74:75]
	v_lshlrev_b32_e32 v80, 16, v95
	v_pk_mul_f32 v[78:79], v[74:75], v[82:83]
	v_cvt_pk_bf16_f32 v73, v74, v75
	v_lshlrev_b32_e32 v74, 16, v94
	v_and_b32_e32 v75, 0xffff0000, v94
	v_and_b32_e32 v81, 0xffff0000, v95
	v_pk_mul_f32 v[74:75], v[146:147], v[74:75]
	v_pk_mul_f32 v[80:81], v[148:149], v[80:81]
	v_cvt_pk_bf16_f32 v77, v78, v79
	v_pk_mul_f32 v[78:79], v[74:75], v[140:141]
	v_cvt_pk_bf16_f32 v74, v74, v75
	v_cvt_pk_bf16_f32 v75, v80, v81
	ds_write_b128 v84, v[72:75] offset:8192
	v_and_b32_e32 v72, 0xfffff0, v70
	v_lshlrev_b32_e32 v73, 1, v70
	v_and_or_b32 v72, v73, 8, v72
	v_lshrrev_b32_e32 v72, 1, v72
	v_bfe_u32 v74, v66, 2, 2
	v_lshrrev_b32_e32 v73, 1, v70
	v_or_b32_e32 v72, v72, v74
	v_and_b32_e32 v74, 3, v70
	v_and_or_b32 v73, v73, 4, v74
	v_pk_mul_f32 v[82:83], v[80:81], v[142:143]
	v_lshlrev_b32_e32 v73, 6, v73
	v_and_b32_e32 v71, 48, v71
	v_lshl_add_u32 v72, v72, 9, 0
	s_cmp_lt_u32 s49, 62
	v_cvt_pk_bf16_f32 v78, v78, v79
	v_cvt_pk_bf16_f32 v79, v82, v83
	v_add3_u32 v71, v72, v73, v71
	s_cselect_b64 s[36:37], -1, 0
	s_cmp_gt_u32 s49, 61
	ds_write_b128 v71, v[76:79] offset:16384
	s_cbranch_scc1 .LBB0_977
	s_add_i32 s14, s20, -1
	s_add_i32 s15, s48, -2
	s_and_b64 s[0:1], s[12:13], exec
	s_cselect_b32 s0, s14, s15
	s_lshl_b32 s0, s0, 5
	v_sub_u32_e32 v71, 31, v70
	v_cndmask_b32_e64 v70, v71, v70, s[12:13]
	s_add_i32 s0, s0, s47
	v_and_b32_e32 v72, 0x78, v68
	v_add_u32_e32 v73, s0, v70
	v_mov_b64_e32 v[70:71], s[30:31]
	v_mad_i64_i32 v[70:71], s[14:15], v73, s39, v[70:71]
	v_lshlrev_b32_e32 v84, 1, v72
	v_lshl_add_u64 v[70:71], v[70:71], 0, v[84:85]
	global_load_dwordx4 v[88:91], v[70:71], off
	global_load_dwordx4 v[92:95], v[70:71], off offset:1024
	v_sub_u32_e32 v70, 31, v67
	v_cndmask_b32_e64 v70, v70, v67, s[12:13]
	v_sub_u32_e32 v67, 15, v67
	v_add_u32_e32 v72, s0, v70
	v_mov_b64_e32 v[70:71], s[34:35]
	v_and_b32_e32 v68, 0xf8, v68
	v_cndmask_b32_e64 v67, v67, v69, s[12:13]
	v_mad_i64_i32 v[72:73], s[14:15], v72, s39, v[70:71]
	v_lshlrev_b32_e32 v84, 1, v68
	v_add_u32_e32 v67, s0, v67
	v_lshl_add_u64 v[72:73], v[72:73], 0, v[84:85]
	v_mad_i64_i32 v[68:69], s[14:15], v67, s39, v[70:71]
	v_lshl_add_u64 v[68:69], v[68:69], 0, v[84:85]
	global_load_dwordx4 v[96:99], v[72:73], off offset:2048
	global_load_dwordx4 v[100:103], v[68:69], off offset:2048
	s_and_b64 vcc, exec, s[8:9]
	s_cbranch_vccnz .LBB0_977
	v_and_b32_e32 v67, 31, v66
	v_bitop3_b32 v68, v66, 31, v66 bitop3:0xc
	v_cndmask_b32_e64 v67, v68, v67, s[12:13]
	v_or_b32_e32 v67, s0, v67
	v_lshlrev_b32_e32 v84, 7, v67
	v_lshl_add_u64 v[68:69], s[26:27], 0, v[84:85]
	v_and_b32_e32 v84, 32, v66
	v_lshl_add_u64 v[66:67], v[68:69], 0, v[84:85]
	global_load_dwordx4 v[104:107], v[66:67], off
	global_load_dwordx4 v[108:111], v[66:67], off offset:16
.LBB0_977:
	v_mov_b32_e32 v86, v159
	s_waitcnt lgkmcnt(0)
	s_barrier
	v_cvt_pk_bf16_f32 v194, v58, v59
	v_and_b32_e32 v84, 31, v86
	v_bfe_u32 v192, v86, 5, 1
	v_lshlrev_b32_e32 v87, 4, v86
	v_lshlrev_b32_e32 v200, 4, v192
	v_lshlrev_b32_e32 v193, 8, v84
	v_and_b32_e32 v201, 0x70, v87
	v_bitop3_b32 v66, v201, v193, v200 bitop3:0xde
	v_add_u32_e32 v70, 0, v66
	ds_read_b128 v[66:69], v70 offset:8192
	ds_read_b128 v[70:73], v70
	s_waitcnt lgkmcnt(0)
	v_mfma_f32_32x32x16_bf16 v[68:83], v[66:69], v[70:73], 0
	v_or_b32_e32 v66, 32, v200
	v_bitop3_b32 v66, v66, v193, v201 bitop3:0xde
	v_add_u32_e32 v66, 0, v66
	ds_read_b128 v[140:143], v66 offset:8192
	ds_read_b128 v[144:147], v66
	v_or_b32_e32 v66, 64, v200
	v_bitop3_b32 v66, v66, v193, v201 bitop3:0xde
	v_add_u32_e32 v66, 0, v66
	s_waitcnt lgkmcnt(0)
	v_mfma_f32_32x32x16_bf16 v[68:83], v[140:143], v[144:147], v[68:83]
	ds_read_b128 v[140:143], v66 offset:8192
	ds_read_b128 v[144:147], v66
	v_or_b32_e32 v66, 0x60, v200
	v_bitop3_b32 v66, v66, v193, v201 bitop3:0xde
	v_add_u32_e32 v66, 0, v66
	ds_read_b128 v[148:151], v66 offset:8192
	v_and_b32_e32 v67, 63, v86
	v_lshlrev_b32_e32 v67, 3, v67
	s_waitcnt lgkmcnt(0)
	v_mfma_f32_32x32x16_bf16 v[68:83], v[140:143], v[144:147], v[68:83]
	ds_read_b128 v[140:143], v66
	v_or_b32_e32 v66, 0x80, v200
	v_bitop3_b32 v66, v66, v193, v201 bitop3:0xde
	v_add_u32_e32 v66, 0, v66
	ds_read_b128 v[144:147], v66 offset:8192
	v_and_b32_e32 v87, 0xc0, v87
	v_and_b32_e32 v153, 0x100, v67
	s_waitcnt lgkmcnt(0)
	v_mfma_f32_32x32x16_bf16 v[68:83], v[148:151], v[140:143], v[68:83]
	ds_read_b128 v[140:143], v66
	v_or_b32_e32 v66, 0xa0, v200
	v_bitop3_b32 v66, v66, v193, v201 bitop3:0xde
	v_add_u32_e32 v66, 0, v66
	ds_read_b128 v[148:151], v66 offset:8192
	v_lshlrev_b32_e32 v86, 1, v86
	v_and_b32_e32 v152, 32, v86
	s_waitcnt lgkmcnt(0)
	v_mfma_f32_32x32x16_bf16 v[68:83], v[144:147], v[140:143], v[68:83]
	ds_read_b128 v[140:143], v66
	v_or_b32_e32 v66, 0xc0, v200
	v_bitop3_b32 v66, v66, v193, v201 bitop3:0xde
	v_add_u32_e32 v66, 0, v66
	ds_read_b128 v[144:147], v66 offset:8192
	v_lshlrev_b32_e32 v86, 2, v192
	v_cmp_le_u32_e32 vcc, v86, v84
	s_waitcnt lgkmcnt(0)
	v_mfma_f32_32x32x16_bf16 v[68:83], v[148:151], v[140:143], v[68:83]
	ds_read_b128 v[140:143], v66
	v_or_b32_e32 v148, 0xe0, v200
	v_and_or_b32 v66, v67, 24, v87
	v_bitop3_b32 v67, v148, v193, v201 bitop3:0xde
	v_add_u32_e32 v67, 0, v67
	ds_read_b128 v[148:151], v67 offset:8192
	v_or3_b32 v204, v66, v152, v153
	s_waitcnt lgkmcnt(0)
	v_mfma_f32_32x32x16_bf16 v[68:83], v[144:147], v[140:143], v[68:83]
	ds_read_b128 v[140:143], v67
	v_or_b32_e32 v191, 2, v86
	v_or_b32_e32 v190, 3, v86
	v_or_b32_e32 v189, 8, v86
	v_or_b32_e32 v188, 9, v86
	v_or_b32_e32 v187, 10, v86
	v_lshlrev_b32_e32 v203, 3, v192
	s_waitcnt lgkmcnt(0)
	v_mfma_f32_32x32x16_bf16 v[68:83], v[148:151], v[140:143], v[68:83]
	v_add_u32_e32 v205, 0, v193
	v_or_b32_e32 v186, 11, v86
	v_or_b32_e32 v185, 16, v86
	v_or_b32_e32 v184, 17, v86
	v_or_b32_e32 v183, 18, v86
	v_or_b32_e32 v182, 19, v86
	v_or_b32_e32 v181, 24, v86
	s_nop 4
	v_cvt_pk_bf16_f32 v66, v68, s0
	v_cndmask_b32_e32 v66, 0, v66, vcc
	v_cvt_pk_bf16_f32 v67, v69, s0
	v_cmp_lt_u32_e32 vcc, v86, v84
	v_add3_u32 v69, v205, v201, v203
	ds_read2_b64 v[142:145], v69 offset1:16
	v_cndmask_b32_e32 v67, 0, v67, vcc
	v_perm_b32 v152, v67, v66, s45
	v_cvt_pk_bf16_f32 v66, v70, s0
	v_cmp_le_u32_e32 vcc, v191, v84
	v_cvt_pk_bf16_f32 v67, v71, s0
	v_or_b32_e32 v70, 16, v203
	v_cndmask_b32_e32 v66, 0, v66, vcc
	v_cmp_le_u32_e32 vcc, v190, v84
	v_xad_u32 v70, v70, v201, v205
	s_waitcnt lgkmcnt(0)
	v_mov_b32_e32 v71, v143
	v_cndmask_b32_e32 v67, 0, v67, vcc
	v_perm_b32 v153, v67, v66, s45
	v_cvt_pk_bf16_f32 v66, v72, s0
	v_cmp_le_u32_e32 vcc, v189, v84
	v_cvt_pk_bf16_f32 v67, v73, s0
	ds_read_b64 v[72:73], v70
	v_cndmask_b32_e32 v66, 0, v66, vcc
	v_cmp_le_u32_e32 vcc, v188, v84
	v_mov_b32_e32 v70, v142
	v_cvt_pk_bf16_f32 v68, v54, v55
	v_cndmask_b32_e32 v67, 0, v67, vcc
	v_perm_b32 v154, v67, v66, s45
	v_cvt_pk_bf16_f32 v66, v74, s0
	v_cmp_le_u32_e32 vcc, v187, v84
	v_cvt_pk_bf16_f32 v67, v75, s0
	v_or_b32_e32 v74, 32, v203
	v_cndmask_b32_e32 v66, 0, v66, vcc
	v_cmp_le_u32_e32 vcc, v186, v84
	v_or_b32_e32 v75, 48, v203
	v_cvt_pk_bf16_f32 v69, v56, v57
	v_cndmask_b32_e32 v67, 0, v67, vcc
	v_perm_b32 v155, v67, v66, s45
	v_cvt_pk_bf16_f32 v66, v76, s0
	v_cmp_le_u32_e32 vcc, v185, v84
	v_cvt_pk_bf16_f32 v67, v77, s0
	v_or_b32_e32 v76, 64, v203
	v_cndmask_b32_e32 v66, 0, v66, vcc
	v_cmp_le_u32_e32 vcc, v184, v84
	v_xad_u32 v74, v74, v201, v205
	v_xad_u32 v75, v75, v201, v205
	v_cndmask_b32_e32 v67, 0, v67, vcc
	v_perm_b32 v140, v67, v66, s45
	v_cvt_pk_bf16_f32 v66, v78, s0
	v_cmp_le_u32_e32 vcc, v183, v84
	v_cvt_pk_bf16_f32 v67, v79, s0
	v_xad_u32 v76, v76, v201, v205
	v_cndmask_b32_e32 v66, 0, v66, vcc
	v_cmp_le_u32_e32 vcc, v182, v84
	v_cvt_pk_bf16_f32 v151, v81, s0
	ds_read_b64 v[146:147], v74
	ds_read_b64 v[148:149], v75
	ds_read_b64 v[192:193], v76
	v_cndmask_b32_e32 v67, 0, v67, vcc
	v_perm_b32 v141, v67, v66, s45
	v_cvt_pk_bf16_f32 v66, v80, s0
	v_cmp_le_u32_e32 vcc, v181, v84
	v_cvt_pk_bf16_f32 v67, v52, v53
	v_or_b32_e32 v143, 0x50, v203
	v_cndmask_b32_e32 v150, 0, v66, vcc
	v_cvt_pk_bf16_f32 v66, v50, v51
	v_cvt_pk_bf16_f32 v195, v60, v61
	v_cvt_pk_bf16_f32 v196, v62, v63
	s_waitcnt lgkmcnt(0)
	v_mfma_f32_32x32x16_bf16 v[66:81], v[70:73], v[66:69], 0
	v_cvt_pk_bf16_f32 v197, v64, v65
	v_xad_u32 v143, v143, v201, v205
	v_or_b32_e32 v167, 25, v86
	v_cmp_le_u32_e32 vcc, v167, v84
	v_or_b32_e32 v163, 26, v86
	v_or_b32_e32 v87, 27, v86
	v_cndmask_b32_e32 v142, 0, v151, vcc
	v_mfma_f32_32x32x16_bf16 v[66:81], v[146:149], v[194:197], v[66:81]
	ds_read_b64 v[194:195], v143
	v_cvt_pk_bf16_f32 v146, v34, v35
	v_cvt_pk_bf16_f32 v147, v36, v37
	v_cvt_pk_bf16_f32 v148, v38, v39
	v_cvt_pk_bf16_f32 v149, v40, v41
	v_perm_b32 v142, v142, v150, s45
	v_or_b32_e32 v143, 0x60, v203
	s_waitcnt lgkmcnt(0)
	v_mfma_f32_32x32x16_bf16 v[66:81], v[192:195], v[146:149], v[66:81]
	v_or_b32_e32 v150, 0x70, v203
	v_or_b32_e32 v151, 0x90, v203
	v_xad_u32 v143, v143, v201, v205
	v_xad_u32 v150, v150, v201, v205
	v_xad_u32 v151, v151, v201, v205
	ds_read_b64 v[196:197], v143
	ds_read_b64 v[198:199], v150
	ds_read_b64 v[150:151], v151
	v_cvt_pk_bf16_f32 v146, v42, v43
	v_cvt_pk_bf16_f32 v147, v44, v45
	v_cvt_pk_bf16_f32 v148, v46, v47
	v_cvt_pk_bf16_f32 v149, v48, v49
	v_or_b32_e32 v143, 0xa0, v203
	v_xad_u32 v143, v143, v201, v205
	s_waitcnt lgkmcnt(0)
	v_mfma_f32_32x32x16_bf16 v[66:81], v[196:199], v[146:149], v[66:81]
	v_mov_b32_e32 v148, v144
	v_mov_b32_e32 v149, v145
	v_cvt_pk_bf16_f32 v144, v18, v19
	v_cvt_pk_bf16_f32 v145, v20, v21
	v_cvt_pk_bf16_f32 v146, v22, v23
	v_cvt_pk_bf16_f32 v147, v24, v25
	v_or_b32_e32 v192, 0xd0, v203
	v_xad_u32 v194, v192, v201, v205
	v_mfma_f32_32x32x16_bf16 v[66:81], v[148:151], v[144:147], v[66:81]
	v_or_b32_e32 v146, 0xb0, v203
	v_xad_u32 v146, v146, v201, v205
	ds_read_b64 v[148:149], v143
	ds_read_b64 v[150:151], v146
	v_cvt_pk_bf16_f32 v144, v26, v27
	v_cvt_pk_bf16_f32 v145, v28, v29
	v_cvt_pk_bf16_f32 v146, v30, v31
	v_cvt_pk_bf16_f32 v147, v32, v33
	v_or_b32_e32 v143, 0xc0, v203
	v_xad_u32 v143, v143, v201, v205
	s_waitcnt lgkmcnt(0)
	v_mfma_f32_32x32x16_bf16 v[66:81], v[148:151], v[144:147], v[66:81]
	ds_read_b64 v[192:193], v143
	ds_read_b64 v[194:195], v194
	v_cvt_pk_bf16_f32 v82, v82, s0
	v_cmp_le_u32_e32 vcc, v163, v84
	v_cvt_pk_bf16_f32 v83, v83, s0
	v_cvt_pk_bf16_f32 v144, v2, v3
	v_cndmask_b32_e32 v82, 0, v82, vcc
	v_cmp_le_u32_e32 vcc, v87, v84
	v_cvt_pk_bf16_f32 v145, v4, v5
	v_cvt_pk_bf16_f32 v146, v6, v7
	v_cvt_pk_bf16_f32 v147, v8, v9
	v_cndmask_b32_e32 v83, 0, v83, vcc
	v_perm_b32 v143, v83, v82, s45
	s_waitcnt lgkmcnt(0)
	v_mfma_f32_32x32x16_bf16 v[66:81], v[192:195], v[144:147], v[66:81]
	v_or_b32_e32 v82, 0xe0, v203
	v_xad_u32 v82, v82, v201, v205
	v_or_b32_e32 v83, 0xf0, v203
	v_xad_u32 v83, v83, v201, v205
	ds_read_b64 v[144:145], v82
	ds_read_b64 v[146:147], v83
	v_cvt_pk_bf16_f32 v148, v10, v11
	v_cvt_pk_bf16_f32 v149, v12, v13
	v_cvt_pk_bf16_f32 v150, v14, v15
	v_cvt_pk_bf16_f32 v151, v16, v17
	v_add_u32_e32 v202, s7, v204
	v_permlane32_swap_b32_e32 v152, v154
	s_waitcnt lgkmcnt(0)
	v_mfma_f32_32x32x16_bf16 v[66:81], v[144:147], v[148:151], v[66:81]
	ds_read_b64_tr_b16 v[144:145], v202 offset:0
	ds_read_b64_tr_b16 v[146:147], v202 offset:0x800
	ds_read_b64_tr_b16 v[148:149], v202 offset:0x1000
	ds_read_b64_tr_b16 v[150:151], v202 offset:0x1800
	s_waitcnt lgkmcnt(0)
	v_permlane32_swap_b32_e32 v153, v155
	v_permlane32_swap_b32_e32 v140, v142
	v_permlane32_swap_b32_e32 v141, v143
	v_add_u32_e32 v82, 0, v200
	v_add_u32_e32 v83, 0x14200, v82
	v_mfma_f32_32x32x16_bf16 v[66:81], v[152:155], v[144:147], v[66:81]
	ds_read_b128 v[152:155], v83
	v_add_u32_e32 v83, 0x14220, v82
	ds_read_b128 v[192:195], v83
	v_add_u32_e32 v83, 0x14240, v82
	ds_read_b128 v[196:199], v83
	v_add_u32_e32 v83, 0x14260, v82
	s_add_i32 s51, 0, 0x4000
	ds_read_b128 v[200:203], v83
	s_waitcnt lgkmcnt(0)
	v_pk_mul_f32 v[50:51], v[50:51], v[152:153]
	v_add_u32_e32 v83, s51, v204
	ds_read_b64_tr_b16 v[152:153], v83 offset:0
	v_pk_mul_f32 v[52:53], v[52:53], v[154:155]
	ds_read_b64_tr_b16 v[154:155], v83 offset:0x800
	v_pk_mul_f32 v[54:55], v[54:55], v[192:193]
	ds_read_b64_tr_b16 v[192:193], v83 offset:0x1000
	v_pk_mul_f32 v[56:57], v[56:57], v[194:195]
	ds_read_b64_tr_b16 v[194:195], v83 offset:0x1800
	s_waitcnt lgkmcnt(0)
	v_pk_mul_f32 v[62:63], v[62:63], v[200:201]
	v_pk_mul_f32 v[58:59], v[58:59], v[196:197]
	v_pk_mul_f32 v[64:65], v[64:65], v[202:203]
	v_pk_mul_f32 v[60:61], v[60:61], v[198:199]
	s_nop 1
	v_mfma_f32_32x32x16_bf16 v[50:65], v[152:155], v[144:147], v[50:65]
	v_add_u32_e32 v152, 0x14280, v82
	ds_read_b128 v[152:155], v152
	v_add_u32_e32 v196, 0x142c0, v82
	v_add_u32_e32 v200, 0x142e0, v82
	ds_read_b128 v[196:199], v196
	ds_read_b128 v[200:203], v200
	s_waitcnt lgkmcnt(0)
	v_pk_mul_f32 v[42:43], v[42:43], v[196:197]
	v_mfma_f32_32x32x16_bf16 v[50:65], v[192:195], v[148:151], v[50:65]
	v_add_u32_e32 v192, 0x142a0, v82
	ds_read_b128 v[192:195], v192
	v_mul_f32_e64 v34, v34, v152
	v_mul_f32_e64 v35, v35, v153
	ds_read_b64_tr_b16 v[152:153], v83 offset:0x200
	v_mul_f32_e64 v36, v36, v154
	v_mul_f32_e64 v37, v37, v155
	ds_read_b64_tr_b16 v[154:155], v83 offset:0xa00
	s_waitcnt lgkmcnt(0)
	v_pk_mul_f32 v[38:39], v[38:39], v[192:193]
	ds_read_b64_tr_b16 v[192:193], v83 offset:0x1200
	v_pk_mul_f32 v[40:41], v[40:41], v[194:195]
	ds_read_b64_tr_b16 v[194:195], v83 offset:0x1a00
	s_waitcnt lgkmcnt(0)
	v_pk_mul_f32 v[46:47], v[46:47], v[200:201]
	v_pk_mul_f32 v[48:49], v[48:49], v[202:203]
	v_pk_mul_f32 v[44:45], v[44:45], v[198:199]
	s_nop 1
	v_mfma_f32_32x32x16_bf16 v[34:49], v[152:155], v[144:147], v[34:49]
	v_add_u32_e32 v152, 0x14300, v82
	ds_read_b128 v[152:155], v152
	v_add_u32_e32 v196, 0x14340, v82
	v_add_u32_e32 v200, 0x14360, v82
	ds_read_b128 v[196:199], v196
	ds_read_b128 v[200:203], v200
	s_waitcnt lgkmcnt(0)
	v_pk_mul_f32 v[26:27], v[26:27], v[196:197]
	v_mfma_f32_32x32x16_bf16 v[34:49], v[192:195], v[148:151], v[34:49]
	v_add_u32_e32 v192, 0x14320, v82
	ds_read_b128 v[192:195], v192
	v_mul_f32_e64 v18, v18, v152
	v_mul_f32_e64 v19, v19, v153
	ds_read_b64_tr_b16 v[152:153], v83 offset:0x400
	v_mul_f32_e64 v20, v20, v154
	v_mul_f32_e64 v21, v21, v155
	ds_read_b64_tr_b16 v[154:155], v83 offset:0xc00
	s_waitcnt lgkmcnt(0)
	v_pk_mul_f32 v[22:23], v[22:23], v[192:193]
	ds_read_b64_tr_b16 v[192:193], v83 offset:0x1400
	v_pk_mul_f32 v[24:25], v[24:25], v[194:195]
	ds_read_b64_tr_b16 v[194:195], v83 offset:0x1c00
	s_waitcnt lgkmcnt(0)
	v_pk_mul_f32 v[30:31], v[30:31], v[200:201]
	v_pk_mul_f32 v[32:33], v[32:33], v[202:203]
	v_pk_mul_f32 v[28:29], v[28:29], v[198:199]
	s_nop 1
	v_mfma_f32_32x32x16_bf16 v[18:33], v[152:155], v[144:147], v[18:33]
	v_add_u32_e32 v152, 0x14380, v82
	ds_read_b128 v[152:155], v152
	v_add_u32_e32 v196, 0x143c0, v82
	ds_read_b128 v[196:199], v196
	s_waitcnt lgkmcnt(0)
	v_pk_mul_f32 v[10:11], v[10:11], v[196:197]
	v_mfma_f32_32x32x16_bf16 v[18:33], v[192:195], v[148:151], v[18:33]
	v_add_u32_e32 v192, 0x143a0, v82
	v_add_u32_e32 v82, 0x143e0, v82
	ds_read_b128 v[192:195], v192
	ds_read_b128 v[200:203], v82
	v_mul_f32_e64 v2, v2, v152
	v_mul_f32_e64 v3, v3, v153
	v_pk_mul_f32 v[4:5], v[4:5], v[154:155]
	v_pk_mul_f32 v[12:13], v[12:13], v[198:199]
	v_mfma_f32_32x32x16_bf16 v[66:81], v[140:143], v[148:151], v[66:81]
	ds_read_b64_tr_b16 v[140:141], v83 offset:0x600
	ds_read_b64_tr_b16 v[142:143], v83 offset:0xe00
	ds_read_b64_tr_b16 v[152:153], v83 offset:0x1600
	ds_read_b64_tr_b16 v[154:155], v83 offset:0x1e00
	s_waitcnt lgkmcnt(0)
	s_waitcnt lgkmcnt(0)
	v_mul_f32_e64 v14, v14, v200
	v_mul_f32_e64 v15, v15, v201
	v_mul_f32_e64 v6, v6, v192
	v_mul_f32_e64 v7, v7, v193
	v_pk_mul_f32 v[16:17], v[16:17], v[202:203]
	v_pk_mul_f32 v[8:9], v[8:9], v[194:195]
	s_and_b64 s[0:1], s[12:13], exec
	s_cselect_b32 s0, s49, s48
	v_lshlrev_b32_e32 v84, 1, v84
	s_lshl_b32 s0, s0, 5
	v_lshl_add_u64 v[82:83], s[28:29], 0, v[84:85]
	v_xor_b32_e32 v84, 31, v86
	s_add_i32 s0, s0, s47
	v_cndmask_b32_e64 v84, v84, v86, s[12:13]
	v_or_b32_e32 v84, s0, v84
	v_lshlrev_b32_e32 v84, 11, v84
	v_mfma_f32_32x32x16_bf16 v[2:17], v[140:143], v[144:147], v[2:17]
	v_cvt_pk_bf16_f32 v66, v66, s0
	v_lshl_add_u64 v[140:141], v[82:83], 0, v[84:85]
	global_store_short v[140:141], v66, off
	v_cvt_pk_bf16_f32 v140, v67, s0
	v_or_b32_e32 v66, 1, v86
	v_xor_b32_e32 v67, 30, v86
	v_cndmask_b32_e64 v66, v67, v66, s[12:13]
	v_or_b32_e32 v66, s0, v66
	v_lshlrev_b32_e32 v84, 11, v66
	v_lshl_add_u64 v[66:67], v[82:83], 0, v[84:85]
	global_store_short v[66:67], v140, off
	v_xor_b32_e32 v66, 29, v86
	v_cndmask_b32_e64 v66, v66, v191, s[12:13]
	v_or_b32_e32 v66, s0, v66
	v_lshlrev_b32_e32 v84, 11, v66
	v_cvt_pk_bf16_f32 v68, v68, s0
	v_lshl_add_u64 v[66:67], v[82:83], 0, v[84:85]
	global_store_short v[66:67], v68, off
	v_xor_b32_e32 v66, 28, v86
	v_cndmask_b32_e64 v66, v66, v190, s[12:13]
	v_or_b32_e32 v66, s0, v66
	v_lshlrev_b32_e32 v84, 11, v66
	v_cvt_pk_bf16_f32 v68, v69, s0
	v_lshl_add_u64 v[66:67], v[82:83], 0, v[84:85]
	global_store_short v[66:67], v68, off
	v_xor_b32_e32 v66, 23, v86
	v_cndmask_b32_e64 v66, v66, v189, s[12:13]
	v_or_b32_e32 v66, s0, v66
	v_lshlrev_b32_e32 v84, 11, v66
	v_cvt_pk_bf16_f32 v68, v70, s0
	v_lshl_add_u64 v[66:67], v[82:83], 0, v[84:85]
	global_store_short v[66:67], v68, off
	v_xor_b32_e32 v66, 22, v86
	v_cndmask_b32_e64 v66, v66, v188, s[12:13]
	v_or_b32_e32 v66, s0, v66
	v_lshlrev_b32_e32 v84, 11, v66
	v_cvt_pk_bf16_f32 v68, v71, s0
	v_lshl_add_u64 v[66:67], v[82:83], 0, v[84:85]
	global_store_short v[66:67], v68, off
	v_xor_b32_e32 v66, 21, v86
	v_cndmask_b32_e64 v66, v66, v187, s[12:13]
	v_or_b32_e32 v66, s0, v66
	v_lshlrev_b32_e32 v84, 11, v66
	v_cvt_pk_bf16_f32 v68, v72, s0
	v_lshl_add_u64 v[66:67], v[82:83], 0, v[84:85]
	global_store_short v[66:67], v68, off
	v_xor_b32_e32 v66, 20, v86
	v_cndmask_b32_e64 v66, v66, v186, s[12:13]
	v_or_b32_e32 v66, s0, v66
	v_lshlrev_b32_e32 v84, 11, v66
	v_cvt_pk_bf16_f32 v68, v73, s0
	v_lshl_add_u64 v[66:67], v[82:83], 0, v[84:85]
	global_store_short v[66:67], v68, off
	v_xor_b32_e32 v66, 15, v86
	v_cndmask_b32_e64 v66, v66, v185, s[12:13]
	v_or_b32_e32 v66, s0, v66
	v_lshlrev_b32_e32 v84, 11, v66
	v_cvt_pk_bf16_f32 v68, v74, s0
	v_lshl_add_u64 v[66:67], v[82:83], 0, v[84:85]
	global_store_short v[66:67], v68, off
	v_xor_b32_e32 v66, 14, v86
	v_cndmask_b32_e64 v66, v66, v184, s[12:13]
	v_or_b32_e32 v66, s0, v66
	v_lshlrev_b32_e32 v84, 11, v66
	v_cvt_pk_bf16_f32 v68, v75, s0
	v_lshl_add_u64 v[66:67], v[82:83], 0, v[84:85]
	global_store_short v[66:67], v68, off
	v_xor_b32_e32 v66, 13, v86
	v_cndmask_b32_e64 v66, v66, v183, s[12:13]
	v_or_b32_e32 v66, s0, v66
	v_lshlrev_b32_e32 v84, 11, v66
	v_cvt_pk_bf16_f32 v68, v76, s0
	v_lshl_add_u64 v[66:67], v[82:83], 0, v[84:85]
	global_store_short v[66:67], v68, off
	v_xor_b32_e32 v66, 12, v86
	v_cndmask_b32_e64 v66, v66, v182, s[12:13]
	v_or_b32_e32 v66, s0, v66
	v_lshlrev_b32_e32 v84, 11, v66
	v_cvt_pk_bf16_f32 v68, v77, s0
	v_lshl_add_u64 v[66:67], v[82:83], 0, v[84:85]
	global_store_short v[66:67], v68, off
	v_xor_b32_e32 v66, 7, v86
	v_cndmask_b32_e64 v66, v66, v181, s[12:13]
	v_or_b32_e32 v66, s0, v66
	v_lshlrev_b32_e32 v84, 11, v66
	v_cvt_pk_bf16_f32 v68, v78, s0
	v_lshl_add_u64 v[66:67], v[82:83], 0, v[84:85]
	global_store_short v[66:67], v68, off
	v_xor_b32_e32 v66, 6, v86
	v_cndmask_b32_e64 v66, v66, v167, s[12:13]
	v_or_b32_e32 v66, s0, v66
	v_lshlrev_b32_e32 v84, 11, v66
	v_cvt_pk_bf16_f32 v68, v79, s0
	v_lshl_add_u64 v[66:67], v[82:83], 0, v[84:85]
	global_store_short v[66:67], v68, off
	v_xor_b32_e32 v66, 5, v86
	v_cndmask_b32_e64 v66, v66, v163, s[12:13]
	v_mfma_f32_32x32x16_bf16 v[2:17], v[152:155], v[148:151], v[2:17]
	v_or_b32_e32 v66, s0, v66
	v_lshlrev_b32_e32 v84, 11, v66
	v_cvt_pk_bf16_f32 v68, v80, s0
	v_lshl_add_u64 v[66:67], v[82:83], 0, v[84:85]
	global_store_short v[66:67], v68, off
	v_xor_b32_e32 v66, 4, v86
	v_cndmask_b32_e64 v66, v66, v87, s[12:13]
	v_or_b32_e32 v66, s0, v66
	v_lshlrev_b32_e32 v84, 11, v66
	v_cvt_pk_bf16_f32 v68, v81, s0
	v_lshl_add_u64 v[66:67], v[82:83], 0, v[84:85]
	v_mov_b32_e32 v82, v159
	s_and_b64 vcc, exec, s[8:9]
	global_store_short v[66:67], v68, off
	s_cbranch_vccnz .LBB0_981
	v_cvt_pk_bf16_f32 v66, v132, v133
	v_cvt_pk_bf16_f32 v67, v134, v135
	v_cvt_pk_bf16_f32 v68, v136, v137
	v_cvt_pk_bf16_f32 v69, v138, v139
	v_and_b32_e32 v87, 63, v82
	v_and_b32_e32 v83, 31, v82
	v_mfma_f32_32x32x16_bf16 v[66:81], v[66:69], v[128:131], 0
	s_nop 11
	v_add_f32_e32 v66, v180, v66
	v_mul_f32_e64 v84, |v66|, s40
	v_exp_f32_e32 v84, v84
	v_add_f32_e32 v67, v180, v67
	v_mul_f32_e64 v86, |v67|, s40
	v_exp_f32_e32 v86, v86
	v_add_f32_e32 v84, 1.0, v84
	v_cmp_gt_f32_e32 vcc, s41, v84
	v_min_f32_e32 v66, 0, v66
	v_add_f32_e32 v86, 1.0, v86
	v_cndmask_b32_e64 v140, 0, 32, vcc
	v_ldexp_f32 v84, v84, v140
	v_log_f32_e32 v84, v84
	v_cmp_gt_f32_e64 s[14:15], s41, v86
	v_cndmask_b32_e32 v140, 0, v179, vcc
	v_add_f32_e32 v68, v180, v68
	v_cndmask_b32_e64 v141, 0, 32, s[14:15]
	v_ldexp_f32 v86, v86, v141
	v_mul_f32_e32 v141, 0x3f317217, v84
	v_fma_f32 v141, v84, s42, -v141
	v_fmac_f32_e32 v141, 0x3377d1cf, v84
	v_log_f32_e32 v86, v86
	v_fmac_f32_e32 v141, 0x3f317217, v84
	v_cmp_lt_f32_e64 vcc, |v84|, s43
	s_nop 1
	v_cndmask_b32_e32 v84, v84, v141, vcc
	v_sub_f32_e32 v84, v84, v140
	v_sub_f32_e32 v66, v66, v84
	v_fma_f32 v84, v66, s44, 0
	v_min_f32_e32 v66, 0, v67
	v_mul_f32_e32 v67, 0x3f317217, v86
	v_mul_f32_e64 v140, |v68|, s40
	v_fma_f32 v67, v86, s42, -v67
	v_exp_f32_e32 v140, v140
	v_fmac_f32_e32 v67, 0x3377d1cf, v86
	v_fmac_f32_e32 v67, 0x3f317217, v86
	v_cmp_lt_f32_e64 vcc, |v86|, s43
	s_nop 1
	v_cndmask_b32_e32 v67, v86, v67, vcc
	v_cndmask_b32_e64 v86, 0, v179, s[14:15]
	v_sub_f32_e32 v67, v67, v86
	v_add_f32_e32 v86, 1.0, v140
	v_cmp_gt_f32_e32 vcc, s41, v86
	v_sub_f32_e32 v66, v66, v67
	s_nop 0
	v_cndmask_b32_e64 v140, 0, 32, vcc
	v_ldexp_f32 v86, v86, v140
	v_log_f32_e32 v86, v86
	v_fmamk_f32 v140, v66, 0x3d800000, v84
	v_min_f32_e32 v66, 0, v68
	v_add_f32_e32 v68, v180, v69
	v_mul_f32_e64 v69, |v68|, s40
	v_exp_f32_e32 v69, v69
	v_mul_f32_e32 v67, 0x3f317217, v86
	v_fma_f32 v67, v86, s42, -v67
	v_fmac_f32_e32 v67, 0x3377d1cf, v86
	v_fmac_f32_e32 v67, 0x3f317217, v86
	v_cmp_lt_f32_e64 s[14:15], |v86|, s43
	v_add_f32_e32 v69, 1.0, v69
	s_nop 0
	v_cndmask_b32_e64 v67, v86, v67, s[14:15]
	v_cndmask_b32_e32 v86, 0, v179, vcc
	v_cmp_gt_f32_e32 vcc, s41, v69
	v_sub_f32_e32 v67, v67, v86
	v_sub_f32_e32 v66, v66, v67
	v_cndmask_b32_e64 v86, 0, 32, vcc
	v_ldexp_f32 v69, v69, v86
	v_log_f32_e32 v69, v69
	v_fmamk_f32 v86, v66, 0x3d800000, v140
	v_min_f32_e32 v66, 0, v68
	v_add_f32_e32 v68, v180, v70
	v_mul_f32_e32 v67, 0x3f317217, v69
	v_mul_f32_e64 v70, |v68|, s40
	v_fma_f32 v67, v69, s42, -v67
	v_exp_f32_e32 v70, v70
	v_fmac_f32_e32 v67, 0x3377d1cf, v69
	v_fmac_f32_e32 v67, 0x3f317217, v69
	v_cmp_lt_f32_e64 s[14:15], |v69|, s43
	s_nop 1
	v_cndmask_b32_e64 v67, v69, v67, s[14:15]
	v_cndmask_b32_e32 v69, 0, v179, vcc
	v_sub_f32_e32 v67, v67, v69
	v_add_f32_e32 v69, 1.0, v70
	v_cmp_gt_f32_e32 vcc, s41, v69
	v_sub_f32_e32 v66, v66, v67
	v_min_f32_e32 v67, 0, v68
	v_cndmask_b32_e64 v70, 0, 32, vcc
	v_ldexp_f32 v69, v69, v70
	v_log_f32_e32 v69, v69
	v_add_f32_e32 v70, v180, v71
	v_mul_f32_e64 v71, |v70|, s40
	v_exp_f32_e32 v71, v71
	v_mul_f32_e32 v68, 0x3f317217, v69
	v_fma_f32 v68, v69, s42, -v68
	v_fmac_f32_e32 v68, 0x3377d1cf, v69
	v_fmac_f32_e32 v68, 0x3f317217, v69
	v_cmp_lt_f32_e64 s[14:15], |v69|, s43
	v_fmamk_f32 v66, v66, 0x3d800000, v86
	s_nop 0
	v_cndmask_b32_e64 v68, v69, v68, s[14:15]
	v_cndmask_b32_e32 v69, 0, v179, vcc
	v_sub_f32_e32 v68, v68, v69
	v_add_f32_e32 v69, 1.0, v71
	v_cmp_gt_f32_e32 vcc, s41, v69
	v_sub_f32_e32 v67, v67, v68
	v_fma_f32 v141, v67, s44, 0
	v_cndmask_b32_e64 v71, 0, 32, vcc
	v_ldexp_f32 v69, v69, v71
	v_log_f32_e32 v69, v69
	v_min_f32_e32 v67, 0, v70
	v_add_f32_e32 v70, v180, v72
	v_mul_f32_e64 v71, |v70|, s40
	v_mul_f32_e32 v68, 0x3f317217, v69
	v_fma_f32 v68, v69, s42, -v68
	v_exp_f32_e32 v71, v71
	v_fmac_f32_e32 v68, 0x3377d1cf, v69
	v_fmac_f32_e32 v68, 0x3f317217, v69
	v_cmp_lt_f32_e64 s[14:15], |v69|, s43
	s_nop 1
	v_cndmask_b32_e64 v68, v69, v68, s[14:15]
	v_cndmask_b32_e32 v69, 0, v179, vcc
	v_sub_f32_e32 v68, v68, v69
	v_add_f32_e32 v69, 1.0, v71
	v_cmp_gt_f32_e32 vcc, s41, v69
	v_sub_f32_e32 v67, v67, v68
	v_fmamk_f32 v142, v67, 0x3d800000, v141
	v_cndmask_b32_e64 v71, 0, 32, vcc
	v_ldexp_f32 v69, v69, v71
	v_log_f32_e32 v69, v69
	v_min_f32_e32 v67, 0, v70
	v_add_f32_e32 v70, v180, v73
	v_mul_f32_e64 v71, |v70|, s40
	v_mul_f32_e32 v68, 0x3f317217, v69
	v_fma_f32 v68, v69, s42, -v68
	v_exp_f32_e32 v71, v71
	v_fmac_f32_e32 v68, 0x3377d1cf, v69
	v_fmac_f32_e32 v68, 0x3f317217, v69
	v_cmp_lt_f32_e64 s[14:15], |v69|, s43
	s_nop 1
	v_cndmask_b32_e64 v68, v69, v68, s[14:15]
	v_cndmask_b32_e32 v69, 0, v179, vcc
	v_sub_f32_e32 v68, v68, v69
	v_add_f32_e32 v69, 1.0, v71
	v_cmp_gt_f32_e32 vcc, s41, v69
	v_sub_f32_e32 v67, v67, v68
	v_fmamk_f32 v143, v67, 0x3d800000, v142
	v_cndmask_b32_e64 v71, 0, 32, vcc
	v_ldexp_f32 v69, v69, v71
	v_log_f32_e32 v69, v69
	v_min_f32_e32 v67, 0, v70
	v_add_f32_e32 v70, v180, v74
	v_mul_f32_e64 v71, |v70|, s40
	v_mul_f32_e32 v68, 0x3f317217, v69
	v_fma_f32 v68, v69, s42, -v68
	v_exp_f32_e32 v71, v71
	v_fmac_f32_e32 v68, 0x3377d1cf, v69
	v_fmac_f32_e32 v68, 0x3f317217, v69
	v_cmp_lt_f32_e64 s[14:15], |v69|, s43
	s_nop 1
	v_cndmask_b32_e64 v68, v69, v68, s[14:15]
	v_cndmask_b32_e32 v69, 0, v179, vcc
	v_sub_f32_e32 v68, v68, v69
	v_add_f32_e32 v69, 1.0, v71
	v_cmp_gt_f32_e32 vcc, s41, v69
	v_sub_f32_e32 v67, v67, v68
	v_min_f32_e32 v68, 0, v70
	v_cndmask_b32_e64 v71, 0, 32, vcc
	v_ldexp_f32 v69, v69, v71
	v_log_f32_e32 v69, v69
	v_add_f32_e32 v71, v180, v75
	v_mul_f32_e64 v72, |v71|, s40
	v_exp_f32_e32 v72, v72
	v_mul_f32_e32 v70, 0x3f317217, v69
	v_fma_f32 v70, v69, s42, -v70
	v_fmac_f32_e32 v70, 0x3377d1cf, v69
	v_fmac_f32_e32 v70, 0x3f317217, v69
	v_cmp_lt_f32_e64 s[14:15], |v69|, s43
	v_fmamk_f32 v67, v67, 0x3d800000, v143
	s_nop 0
	v_cndmask_b32_e64 v69, v69, v70, s[14:15]
	v_cndmask_b32_e32 v70, 0, v179, vcc
	v_sub_f32_e32 v69, v69, v70
	v_add_f32_e32 v70, 1.0, v72
	v_cmp_gt_f32_e32 vcc, s41, v70
	v_sub_f32_e32 v68, v68, v69
	v_fma_f32 v75, v68, s44, 0
	v_cndmask_b32_e64 v72, 0, 32, vcc
	v_ldexp_f32 v70, v70, v72
	v_log_f32_e32 v70, v70
	v_min_f32_e32 v68, 0, v71
	v_add_f32_e32 v71, v180, v76
	v_mul_f32_e64 v72, |v71|, s40
	v_mul_f32_e32 v69, 0x3f317217, v70
	v_fma_f32 v69, v70, s42, -v69
	v_exp_f32_e32 v72, v72
	v_fmac_f32_e32 v69, 0x3377d1cf, v70
	v_fmac_f32_e32 v69, 0x3f317217, v70
	v_cmp_lt_f32_e64 s[14:15], |v70|, s43
	s_nop 1
	v_cndmask_b32_e64 v69, v70, v69, s[14:15]
	v_cndmask_b32_e32 v70, 0, v179, vcc
	v_sub_f32_e32 v69, v69, v70
	v_add_f32_e32 v70, 1.0, v72
	v_cmp_gt_f32_e32 vcc, s41, v70
	v_sub_f32_e32 v68, v68, v69
	v_fmamk_f32 v76, v68, 0x3d800000, v75
	v_cndmask_b32_e64 v72, 0, 32, vcc
	v_ldexp_f32 v70, v70, v72
	v_log_f32_e32 v70, v70
	v_min_f32_e32 v68, 0, v71
	v_add_f32_e32 v71, v180, v77
	v_mul_f32_e64 v72, |v71|, s40
	v_mul_f32_e32 v69, 0x3f317217, v70
	v_fma_f32 v69, v70, s42, -v69
	v_exp_f32_e32 v72, v72
	v_fmac_f32_e32 v69, 0x3377d1cf, v70
	v_fmac_f32_e32 v69, 0x3f317217, v70
	v_cmp_lt_f32_e64 s[14:15], |v70|, s43
	s_nop 1
	v_cndmask_b32_e64 v69, v70, v69, s[14:15]
	v_cndmask_b32_e32 v70, 0, v179, vcc
	v_sub_f32_e32 v69, v69, v70
	v_add_f32_e32 v70, 1.0, v72
	v_cmp_gt_f32_e32 vcc, s41, v70
	v_sub_f32_e32 v68, v68, v69
	v_fmamk_f32 v77, v68, 0x3d800000, v76
	v_cndmask_b32_e64 v72, 0, 32, vcc
	v_ldexp_f32 v70, v70, v72
	v_log_f32_e32 v70, v70
	v_min_f32_e32 v68, 0, v71
	v_add_f32_e32 v71, v180, v78
	v_mul_f32_e64 v72, |v71|, s40
	v_mul_f32_e32 v69, 0x3f317217, v70
	v_fma_f32 v69, v70, s42, -v69
	v_exp_f32_e32 v72, v72
	v_fmac_f32_e32 v69, 0x3377d1cf, v70
	v_fmac_f32_e32 v69, 0x3f317217, v70
	v_cmp_lt_f32_e64 s[14:15], |v70|, s43
	s_nop 1
	v_cndmask_b32_e64 v69, v70, v69, s[14:15]
	v_cndmask_b32_e32 v70, 0, v179, vcc
	v_sub_f32_e32 v69, v69, v70
	v_add_f32_e32 v70, 1.0, v72
	v_cmp_gt_f32_e32 vcc, s41, v70
	v_sub_f32_e32 v68, v68, v69
	v_min_f32_e32 v69, 0, v71
	v_cndmask_b32_e64 v72, 0, 32, vcc
	v_ldexp_f32 v70, v70, v72
	v_log_f32_e32 v70, v70
	v_add_f32_e32 v72, v180, v79
	v_mul_f32_e64 v73, |v72|, s40
	v_exp_f32_e32 v73, v73
	v_mul_f32_e32 v71, 0x3f317217, v70
	v_fma_f32 v71, v70, s42, -v71
	v_fmac_f32_e32 v71, 0x3377d1cf, v70
	v_fmac_f32_e32 v71, 0x3f317217, v70
	v_cmp_lt_f32_e64 s[14:15], |v70|, s43
	v_fmamk_f32 v68, v68, 0x3d800000, v77
	s_nop 0
	v_cndmask_b32_e64 v70, v70, v71, s[14:15]
	v_cndmask_b32_e32 v71, 0, v179, vcc
	v_sub_f32_e32 v70, v70, v71
	v_add_f32_e32 v71, 1.0, v73
	v_cmp_gt_f32_e32 vcc, s41, v71
	v_sub_f32_e32 v69, v69, v70
	v_fma_f32 v78, v69, s44, 0
	v_cndmask_b32_e64 v73, 0, 32, vcc
	v_ldexp_f32 v71, v71, v73
	v_log_f32_e32 v71, v71
	v_min_f32_e32 v69, 0, v72
	v_add_f32_e32 v72, v180, v80
	v_mul_f32_e64 v73, |v72|, s40
	v_mul_f32_e32 v70, 0x3f317217, v71
	v_fma_f32 v70, v71, s42, -v70
	v_exp_f32_e32 v73, v73
	v_fmac_f32_e32 v70, 0x3377d1cf, v71
	v_fmac_f32_e32 v70, 0x3f317217, v71
	v_cmp_lt_f32_e64 s[14:15], |v71|, s43
	s_nop 1
	v_cndmask_b32_e64 v70, v71, v70, s[14:15]
	v_cndmask_b32_e32 v71, 0, v179, vcc
	v_sub_f32_e32 v70, v70, v71
	v_add_f32_e32 v71, 1.0, v73
	v_cmp_gt_f32_e32 vcc, s41, v71
	v_sub_f32_e32 v69, v69, v70
	v_fmamk_f32 v79, v69, 0x3d800000, v78
	v_cndmask_b32_e64 v73, 0, 32, vcc
	v_ldexp_f32 v71, v71, v73
	v_log_f32_e32 v71, v71
	v_min_f32_e32 v69, 0, v72
	v_add_f32_e32 v72, v180, v81
	v_mul_f32_e64 v73, |v72|, s40
	v_mul_f32_e32 v70, 0x3f317217, v71
	v_fma_f32 v70, v71, s42, -v70
	v_exp_f32_e32 v73, v73
	v_fmac_f32_e32 v70, 0x3377d1cf, v71
	v_fmac_f32_e32 v70, 0x3f317217, v71
	v_cmp_lt_f32_e64 s[14:15], |v71|, s43
	s_nop 1
	v_cndmask_b32_e64 v70, v71, v70, s[14:15]
	v_cndmask_b32_e32 v71, 0, v179, vcc
	v_sub_f32_e32 v70, v70, v71
	v_add_f32_e32 v71, 1.0, v73
	v_cmp_gt_f32_e32 vcc, s41, v71
	v_sub_f32_e32 v69, v69, v70
	v_fmamk_f32 v80, v69, 0x3d800000, v79
	v_cndmask_b32_e64 v73, 0, 32, vcc
	v_ldexp_f32 v71, v71, v73
	v_log_f32_e32 v71, v71
	v_min_f32_e32 v69, 0, v72
	v_mov_b32_e32 v72, v67
	v_mov_b32_e32 v73, v68
	v_mul_f32_e32 v70, 0x3f317217, v71
	v_fma_f32 v70, v71, s42, -v70
	v_fmac_f32_e32 v70, 0x3377d1cf, v71
	v_fmac_f32_e32 v70, 0x3f317217, v71
	v_cmp_lt_f32_e64 s[14:15], |v71|, s43
	s_nop 1
	v_cndmask_b32_e64 v70, v71, v70, s[14:15]
	v_cndmask_b32_e32 v71, 0, v179, vcc
	v_sub_f32_e32 v70, v70, v71
	v_sub_f32_e32 v69, v69, v70
	v_mov_b32_e32 v70, v66
	v_mov_b32_e32 v71, v66
	s_nop 1
	v_permlane32_swap_b32_e32 v70, v71
	v_cmp_gt_u32_e32 vcc, 32, v87
	v_fmamk_f32 v69, v69, 0x3d800000, v80
	v_mov_b32_e32 v74, v69
	v_cndmask_b32_e32 v70, v70, v71, vcc
	v_mov_b32_e32 v71, v67
	s_nop 1
	v_permlane32_swap_b32_e32 v71, v72
	v_cndmask_b32_e32 v71, v71, v72, vcc
	v_mov_b32_e32 v72, v68
	s_nop 1
	v_permlane32_swap_b32_e32 v72, v73
	v_cndmask_b32_e32 v72, v72, v73, vcc
	v_mov_b32_e32 v73, v69
	s_nop 1
	v_permlane32_swap_b32_e32 v73, v74
	v_cndmask_b32_e32 v74, v73, v74, vcc
	v_lshlrev_b32_e32 v73, 6, v82
	v_cndmask_b32_e64 v81, v70, 0, vcc
	v_and_b32_e32 v82, 0x800, v73
	v_lshlrev_b32_e32 v73, 2, v83
	v_add_f32_e32 v83, v81, v84
	v_add3_u32 v82, s4, v73, v82
	v_add_f32_e32 v84, v81, v140
	ds_write2st64_b32 v82, v83, v84 offset1:2
	v_add_f32_e32 v83, v81, v86
	v_add_f32_e32 v84, v81, v66
	ds_write2st64_b32 v82, v83, v84 offset0:4 offset1:6
	v_cndmask_b32_e32 v83, v71, v70, vcc
	v_add_f32_e32 v83, v83, v66
	v_add_f32_e32 v81, v81, v83
	v_add_f32_e32 v83, v141, v81
	v_add_f32_e32 v84, v142, v81
	ds_write2st64_b32 v82, v83, v84 offset0:16 offset1:18
	v_add_f32_e32 v83, v143, v81
	v_add_f32_e32 v84, v67, v81
	ds_write2st64_b32 v82, v83, v84 offset0:20 offset1:22
	v_cndmask_b32_e32 v83, v72, v71, vcc
	v_add_f32_e32 v83, v83, v67
	v_add_f32_e32 v81, v83, v81
	v_add_f32_e32 v75, v75, v81
	v_add_f32_e32 v76, v76, v81
	ds_write2st64_b32 v82, v75, v76 offset0:32 offset1:34
	v_add_f32_e32 v75, v77, v81
	v_add_f32_e32 v76, v68, v81
	ds_write2st64_b32 v82, v75, v76 offset0:36 offset1:38
	v_cndmask_b32_e32 v75, v74, v72, vcc
	v_add_f32_e32 v75, v75, v68
	v_add_f32_e32 v75, v75, v81
	v_add_f32_e32 v76, v78, v75
	v_add_f32_e32 v77, v79, v75
	ds_write2st64_b32 v82, v76, v77 offset0:48 offset1:50
	v_add_f32_e32 v76, v80, v75
	v_add_f32_e32 v75, v69, v75
	ds_write2st64_b32 v82, v76, v75 offset0:52 offset1:54
	s_and_saveexec_b64 s[14:15], vcc
	s_cbranch_execz .LBB0_980
	v_add_f32_e32 v66, v66, v67
	v_add_f32_e32 v67, v68, v69
	v_add_f32_e32 v66, v66, v67
	v_add_f32_e32 v67, v70, v71
	v_add_f32_e32 v66, v67, v66
	v_add_f32_e32 v67, v72, v74
	v_add_f32_e32 v66, v67, v66
	v_mul_f32_e32 v67, 0x3fb8aa3b, v66
	v_exp_f32_e32 v67, v67
	v_add_u32_e32 v68, s5, v73
	ds_write_b32 v68, v66
	v_add_u32_e32 v66, s10, v73
	ds_write_b32 v66, v67

.LBB0_1039:
	s_lshl_b32 s0, s7, 8
	s_add_i32 s0, s0, s97
	s_ashr_i32 s1, s0, 31
	s_add_i32 s10, s0, 8
	s_lshl_b64 s[12:13], s[0:1], 11
	s_ashr_i32 s11, s10, 31
	v_lshl_add_u64 v[18:19], v[92:93], 0, s[12:13]
	v_lshl_add_u64 v[20:21], v[94:95], 0, s[12:13]
	v_mad_i64_i32 v[22:23], s[12:13], s0, v102, v[96:97]
	s_lshl_b64 s[12:13], s[10:11], 11
	s_nop 0
	v_lshl_add_u64 v[24:25], v[92:93], 0, s[12:13]
	v_lshl_add_u64 v[38:39], v[94:95], 0, s[12:13]
	global_load_dwordx4 v[2:5], v[90:91], off
	global_load_dwordx4 v[6:9], v[90:91], off offset:16
	global_load_dwordx4 v[10:13], v[90:91], off offset:2048
	global_load_dwordx4 v[14:17], v[90:91], off offset:2064
	v_mad_i64_i32 v[54:55], s[10:11], s10, v102, v[96:97]
	global_load_dwordx4 v[86:89], v[18:19], off
	global_load_dwordx4 v[50:53], v[18:19], off offset:1024
	global_load_dwordx4 v[82:85], v[20:21], off
	global_load_dwordx4 v[46:49], v[20:21], off offset:1024
	global_load_dwordx4 v[78:81], v[22:23], off
	global_load_dwordx4 v[42:45], v[22:23], off offset:1024
	global_load_dwordx4 v[26:29], v[24:25], off
	global_load_dwordx4 v[30:33], v[24:25], off offset:1024
	global_load_dwordx4 v[34:37], v[38:39], off
	s_nop 0
	global_load_dwordx4 v[38:41], v[38:39], off offset:1024
	s_nop 0
	global_load_dwordx4 v[18:21], v[54:55], off
	global_load_dwordx4 v[22:25], v[54:55], off offset:1024
	s_add_i32 s10, s0, 16
	s_mov_b32 s24, s4
	s_mov_b32 s11, 0
.LBB0_1040:
	s_waitcnt vmcnt(0) lgkmcnt(0)
	v_lshlrev_b32_e32 v100, 16, v89
	v_and_b32_e32 v101, 0xffff0000, v89
	v_lshlrev_b32_e32 v106, 16, v85
	v_and_b32_e32 v107, 0xffff0000, v85
	v_pk_add_f32 v[106:107], v[106:107], v[100:101]
	v_lshlrev_b32_e32 v100, 16, v81
	v_and_b32_e32 v101, 0xffff0000, v81
	v_mul_f32_e32 v81, 0xbfb8aa3b, v100
	v_exp_f32_e32 v81, v81
	v_and_b32_e32 v89, 0xffff0000, v84
	s_min_u32 s0, s11, 29
	s_lshl_b32 s0, s0, 3
	v_add_f32_e32 v81, 1.0, v81
	v_rcp_f32_e32 v108, v81
	v_mul_f32_e32 v81, 0xbfb8aa3b, v101
	v_exp_f32_e32 v81, v81
	s_add_i32 s0, s10, s0
	s_ashr_i32 s1, s0, 31
	s_lshl_b64 s[12:13], s[0:1], 11
	v_add_f32_e32 v81, 1.0, v81
	v_rcp_f32_e32 v109, v81
	v_mad_i64_i32 v[74:75], s[0:1], s0, v102, v[96:97]
	v_mov_b64_e32 v[64:65], v[40:41]
	v_pk_mul_f32 v[100:101], v[108:109], v[100:101]
	v_lshlrev_b32_e32 v108, 16, v88
	v_and_b32_e32 v109, 0xffff0000, v88
	v_lshlrev_b32_e32 v88, 16, v84
	v_pk_add_f32 v[84:85], v[88:89], v[108:109]
	v_lshlrev_b32_e32 v88, 16, v80
	v_and_b32_e32 v89, 0xffff0000, v80
	v_mul_f32_e32 v80, 0xbfb8aa3b, v88
	v_mul_f32_e32 v81, 0xbfb8aa3b, v89
	v_exp_f32_e32 v80, v80
	v_exp_f32_e32 v81, v81
	v_lshlrev_b32_e32 v108, 16, v83
	v_and_b32_e32 v109, 0xffff0000, v83
	v_add_f32_e32 v80, 1.0, v80
	v_add_f32_e32 v81, 1.0, v81
	v_rcp_f32_e32 v80, v80
	v_rcp_f32_e32 v81, v81
	v_mov_b32_e32 v113, v85
	v_mov_b64_e32 v[56:57], v[32:33]
	v_mov_b64_e32 v[62:63], v[38:39]
	v_pk_mul_f32 v[80:81], v[80:81], v[88:89]
	v_lshlrev_b32_e32 v88, 16, v87
	v_and_b32_e32 v89, 0xffff0000, v87
	v_pk_add_f32 v[88:89], v[108:109], v[88:89]
	v_lshlrev_b32_e32 v108, 16, v79
	v_and_b32_e32 v109, 0xffff0000, v79
	v_mul_f32_e32 v79, 0xbfb8aa3b, v108
	v_exp_f32_e32 v79, v79
	v_and_b32_e32 v87, 0xffff0000, v82
	v_mov_b64_e32 v[54:55], v[30:31]
	v_lshl_add_u64 v[30:31], v[92:93], 0, s[12:13]
	v_add_f32_e32 v79, 1.0, v79
	v_rcp_f32_e32 v110, v79
	v_mul_f32_e32 v79, 0xbfb8aa3b, v109
	v_exp_f32_e32 v79, v79
	v_lshl_add_u64 v[38:39], v[94:95], 0, s[12:13]
	s_ashr_i32 s25, s24, 31
	s_lshl_b64 s[26:27], s[24:25], 11
	v_add_f32_e32 v79, 1.0, v79
	v_rcp_f32_e32 v111, v79
	v_mov_b64_e32 v[68:69], v[36:37]
	v_mov_b64_e32 v[60:61], v[28:29]
	v_mov_b64_e32 v[66:67], v[34:35]
	v_pk_mul_f32 v[108:109], v[110:111], v[108:109]
	v_lshlrev_b32_e32 v110, 16, v86
	v_and_b32_e32 v111, 0xffff0000, v86
	v_lshlrev_b32_e32 v86, 16, v82
	v_pk_add_f32 v[82:83], v[86:87], v[110:111]
	v_lshlrev_b32_e32 v86, 16, v78
	v_and_b32_e32 v87, 0xffff0000, v78
	v_mul_f32_e32 v78, 0xbfb8aa3b, v86
	v_mul_f32_e32 v79, 0xbfb8aa3b, v87
	v_exp_f32_e32 v78, v78
	v_exp_f32_e32 v79, v79
	v_mov_b32_e32 v110, v89
	v_mov_b32_e32 v111, v107
	v_add_f32_e32 v78, 1.0, v78
	v_add_f32_e32 v79, 1.0, v79
	v_rcp_f32_e32 v78, v78
	v_rcp_f32_e32 v79, v79
	v_mov_b32_e32 v112, v83
	v_mov_b64_e32 v[58:59], v[26:27]
	global_load_dwordx4 v[26:29], v[30:31], off
	global_load_dwordx4 v[34:37], v[38:39], off
	v_pk_mul_f32 v[78:79], v[78:79], v[86:87]
	v_mov_b32_e32 v86, v88
	v_mov_b32_e32 v87, v106
	v_pk_add_f32 v[86:87], v[86:87], v[110:111]
	v_mov_b32_e32 v110, v82
	v_mov_b32_e32 v111, v84
	v_pk_add_f32 v[110:111], v[110:111], v[112:113]
	global_load_dwordx4 v[70:73], v[74:75], off
	s_nop 0
	global_load_dwordx4 v[30:33], v[30:31], off offset:1024
	s_nop 0
	global_load_dwordx4 v[38:41], v[38:39], off offset:1024
	s_nop 0
	global_load_dwordx4 v[74:77], v[74:75], off offset:1024
	v_pk_add_f32 v[86:87], v[110:111], v[86:87]
	s_add_i32 s11, s11, 1
	v_add_f32_e32 v86, v86, v87
	s_add_i32 s24, s24, 8
	s_cmp_lg_u32 s11, 32
	v_add_f32_dpp v86, v86, v86 quad_perm:[1,0,3,2] row_mask:0xf bank_mask:0xf bound_ctrl:1
	s_nop 1
	v_add_f32_dpp v86, v86, v86 quad_perm:[2,3,0,1] row_mask:0xf bank_mask:0xf bound_ctrl:1
	s_nop 1
	v_add_f32_dpp v86, v86, v86 row_half_mirror row_mask:0xf bank_mask:0xf bound_ctrl:1
	s_nop 1
	v_add_f32_dpp v86, v86, v86 row_mirror row_mask:0xf bank_mask:0xf bound_ctrl:1
	s_nop 0
	v_readlane_b32 s1, v86, 16
	v_readlane_b32 s0, v86, 0
	s_nop 0
	v_mov_b32_e32 v87, s1
	v_readlane_b32 s1, v86, 48
	v_add_f32_e32 v87, s0, v87
	v_readlane_b32 s0, v86, 32
	v_mov_b32_e32 v86, s1
	s_nop 0
	v_add_f32_e32 v86, s0, v86
	v_cndmask_b32_e64 v86, v87, v86, s[8:9]
	v_mul_f32_e32 v86, 0x3b800000, v86
	v_pk_add_f32 v[82:83], v[82:83], v[86:87] op_sel_hi:[1,0] neg_lo:[0,1] neg_hi:[0,1]
	v_pk_add_f32 v[88:89], v[88:89], v[86:87] op_sel_hi:[1,0] neg_lo:[0,1] neg_hi:[0,1]
	v_pk_mul_f32 v[110:111], v[82:83], v[82:83]
	v_pk_mul_f32 v[112:113], v[88:89], v[88:89]
	v_add_f32_e32 v105, v110, v111
	v_pk_add_f32 v[84:85], v[84:85], v[86:87] op_sel_hi:[1,0] neg_lo:[0,1] neg_hi:[0,1]
	v_add_f32_e32 v105, v112, v105
	v_pk_mul_f32 v[114:115], v[84:85], v[84:85]
	v_add_f32_e32 v105, v113, v105
	v_pk_add_f32 v[86:87], v[106:107], v[86:87] op_sel_hi:[1,0] neg_lo:[0,1] neg_hi:[0,1]
	v_add_f32_e32 v105, v114, v105
	v_pk_mul_f32 v[106:107], v[86:87], v[86:87]
	v_add_f32_e32 v105, v115, v105
	v_add_f32_e32 v105, v106, v105
	v_add_f32_e32 v105, v107, v105
	s_nop 1
	v_add_f32_dpp v105, v105, v105 quad_perm:[1,0,3,2] row_mask:0xf bank_mask:0xf bound_ctrl:1
	s_nop 1
	v_add_f32_dpp v105, v105, v105 quad_perm:[2,3,0,1] row_mask:0xf bank_mask:0xf bound_ctrl:1
	s_nop 1
	v_add_f32_dpp v105, v105, v105 row_half_mirror row_mask:0xf bank_mask:0xf bound_ctrl:1
	s_nop 1
	v_add_f32_dpp v105, v105, v105 row_mirror row_mask:0xf bank_mask:0xf bound_ctrl:1
	s_nop 0
	v_readlane_b32 s1, v105, 16
	v_readlane_b32 s0, v105, 0
	s_nop 0
	v_mov_b32_e32 v106, s1
	v_readlane_b32 s1, v105, 48
	v_add_f32_e32 v106, s0, v106
	v_readlane_b32 s0, v105, 32
	v_mov_b32_e32 v105, s1
	s_nop 0
	v_add_f32_e32 v105, s0, v105
	v_cndmask_b32_e64 v105, v106, v105, s[8:9]
	v_fmamk_f32 v105, v105, 0x3b800000, v103
	v_cmp_gt_f32_e32 vcc, s6, v105
	v_mul_f32_e32 v106, 0x4f800000, v105
	s_nop 0
	v_cndmask_b32_e32 v105, v105, v106, vcc
	v_sqrt_f32_e32 v106, v105
	s_nop 0
	v_add_u32_e32 v107, -1, v106
	v_fma_f32 v110, -v107, v106, v105
	v_cmp_ge_f32_e64 s[12:13], 0, v110
	v_add_u32_e32 v110, 1, v106
	s_nop 0
	v_cndmask_b32_e64 v107, v106, v107, s[12:13]
	v_fma_f32 v106, -v110, v106, v105
	v_cmp_lt_f32_e64 s[12:13], 0, v106
	s_nop 1
	v_cndmask_b32_e64 v106, v107, v110, s[12:13]
	v_mul_f32_e32 v107, 0x37800000, v106
	v_cndmask_b32_e32 v106, v106, v107, vcc
	v_cmp_class_f32_e32 vcc, v105, v104
	s_nop 1
	v_cndmask_b32_e32 v105, v106, v105, vcc
	v_div_scale_f32 v106, s[0:1], v105, v105, 1.0
	v_rcp_f32_e32 v107, v106
	s_nop 0
	v_fma_f32 v110, -v106, v107, 1.0
	v_fmac_f32_e32 v107, v110, v107
	v_div_scale_f32 v110, vcc, 1.0, v105, 1.0
	v_mul_f32_e32 v111, v110, v107
	v_fma_f32 v112, -v106, v111, v110
	v_fmac_f32_e32 v111, v112, v107
	v_fma_f32 v106, -v106, v111, v110
	v_div_fmas_f32 v106, v106, v107, v111
	v_div_fixup_f32 v106, v106, v105, 1.0
	v_pk_mul_f32 v[82:83], v[82:83], v[106:107] op_sel_hi:[1,0]
	v_pk_mul_f32 v[84:85], v[84:85], v[106:107] op_sel_hi:[1,0]
	v_pk_mul_f32 v[82:83], v[2:3], v[82:83]
	v_pk_mul_f32 v[84:85], v[6:7], v[84:85]
	v_pk_mul_f32 v[78:79], v[78:79], v[82:83]
	v_pk_mul_f32 v[82:83], v[88:89], v[106:107] op_sel_hi:[1,0]
	v_pk_mul_f32 v[84:85], v[80:81], v[84:85]
	v_pk_mul_f32 v[80:81], v[86:87], v[106:107] op_sel_hi:[1,0]
	v_pk_mul_f32 v[82:83], v[4:5], v[82:83]
	v_pk_mul_f32 v[80:81], v[8:9], v[80:81]
	v_pk_mul_f32 v[82:83], v[108:109], v[82:83]
	v_pk_mul_f32 v[86:87], v[100:101], v[80:81]
	v_cvt_pk_bf16_f32 v80, v78, v79
	v_cvt_pk_bf16_f32 v81, v82, v83
	v_cvt_pk_bf16_f32 v82, v84, v85
	v_cvt_pk_bf16_f32 v83, v86, v87
	v_lshl_add_u64 v[78:79], v[98:99], 0, s[26:27]
	global_store_dwordx4 v[78:79], v[80:83], off
	s_nop 1
	v_lshlrev_b32_e32 v80, 16, v53
	v_and_b32_e32 v81, 0xffff0000, v53
	v_lshlrev_b32_e32 v82, 16, v49
	v_and_b32_e32 v83, 0xffff0000, v49
	v_pk_add_f32 v[82:83], v[82:83], v[80:81]
	v_lshlrev_b32_e32 v80, 16, v45
	v_and_b32_e32 v81, 0xffff0000, v45
	v_mul_f32_e32 v45, 0xbfb8aa3b, v80
	v_exp_f32_e32 v45, v45
	v_and_b32_e32 v53, 0xffff0000, v48
	v_add_f32_e32 v45, 1.0, v45
	v_rcp_f32_e32 v84, v45
	v_mul_f32_e32 v45, 0xbfb8aa3b, v81
	v_exp_f32_e32 v45, v45
	s_nop 0
	v_add_f32_e32 v45, 1.0, v45
	v_rcp_f32_e32 v85, v45
	s_nop 0
	v_pk_mul_f32 v[80:81], v[84:85], v[80:81]
	v_lshlrev_b32_e32 v84, 16, v52
	v_and_b32_e32 v85, 0xffff0000, v52
	v_lshlrev_b32_e32 v52, 16, v48
	v_pk_add_f32 v[48:49], v[52:53], v[84:85]
	v_lshlrev_b32_e32 v52, 16, v44
	v_and_b32_e32 v53, 0xffff0000, v44
	v_mul_f32_e32 v44, 0xbfb8aa3b, v52
	v_mul_f32_e32 v45, 0xbfb8aa3b, v53
	v_exp_f32_e32 v44, v44
	v_exp_f32_e32 v45, v45
	v_lshlrev_b32_e32 v84, 16, v47
	v_and_b32_e32 v85, 0xffff0000, v47
	v_add_f32_e32 v44, 1.0, v44
	v_add_f32_e32 v45, 1.0, v45
	v_rcp_f32_e32 v44, v44
	v_rcp_f32_e32 v45, v45
	v_mov_b32_e32 v89, v49
	v_pk_mul_f32 v[44:45], v[44:45], v[52:53]
	v_lshlrev_b32_e32 v52, 16, v51
	v_and_b32_e32 v53, 0xffff0000, v51
	v_pk_add_f32 v[52:53], v[84:85], v[52:53]
	v_lshlrev_b32_e32 v84, 16, v43
	v_and_b32_e32 v85, 0xffff0000, v43
	v_mul_f32_e32 v43, 0xbfb8aa3b, v84
	v_exp_f32_e32 v43, v43
	v_and_b32_e32 v51, 0xffff0000, v46
	v_add_f32_e32 v43, 1.0, v43
	v_rcp_f32_e32 v86, v43
	v_mul_f32_e32 v43, 0xbfb8aa3b, v85
	v_exp_f32_e32 v43, v43
	s_nop 0
	v_add_f32_e32 v43, 1.0, v43
	v_rcp_f32_e32 v87, v43
	s_nop 0
	v_pk_mul_f32 v[84:85], v[86:87], v[84:85]
	v_lshlrev_b32_e32 v86, 16, v50
	v_and_b32_e32 v87, 0xffff0000, v50
	v_lshlrev_b32_e32 v50, 16, v46
	v_pk_add_f32 v[46:47], v[50:51], v[86:87]
	v_lshlrev_b32_e32 v50, 16, v42
	v_and_b32_e32 v51, 0xffff0000, v42
	v_mul_f32_e32 v42, 0xbfb8aa3b, v50
	v_mul_f32_e32 v43, 0xbfb8aa3b, v51
	v_exp_f32_e32 v42, v42
	v_exp_f32_e32 v43, v43
	v_mov_b32_e32 v86, v53
	v_mov_b32_e32 v87, v83
	v_add_f32_e32 v42, 1.0, v42
	v_add_f32_e32 v43, 1.0, v43
	v_rcp_f32_e32 v42, v42
	v_rcp_f32_e32 v43, v43
	v_mov_b32_e32 v88, v47
	v_pk_mul_f32 v[42:43], v[42:43], v[50:51]
	v_mov_b32_e32 v50, v52
	v_mov_b32_e32 v51, v82
	v_pk_add_f32 v[50:51], v[50:51], v[86:87]
	v_mov_b32_e32 v86, v46
	v_mov_b32_e32 v87, v48
	v_pk_add_f32 v[86:87], v[86:87], v[88:89]
	s_nop 0
	v_pk_add_f32 v[50:51], v[86:87], v[50:51]
	s_nop 0
	v_add_f32_e32 v50, v50, v51
	s_nop 1
	v_add_f32_dpp v50, v50, v50 quad_perm:[1,0,3,2] row_mask:0xf bank_mask:0xf bound_ctrl:1
	s_nop 1
	v_add_f32_dpp v50, v50, v50 quad_perm:[2,3,0,1] row_mask:0xf bank_mask:0xf bound_ctrl:1
	s_nop 1
	v_add_f32_dpp v50, v50, v50 row_half_mirror row_mask:0xf bank_mask:0xf bound_ctrl:1
	s_nop 1
	v_add_f32_dpp v50, v50, v50 row_mirror row_mask:0xf bank_mask:0xf bound_ctrl:1
	s_nop 0
	v_readlane_b32 s1, v50, 16
	v_readlane_b32 s0, v50, 0
	s_nop 0
	v_mov_b32_e32 v51, s1
	v_readlane_b32 s1, v50, 48
	v_add_f32_e32 v51, s0, v51
	v_readlane_b32 s0, v50, 32
	v_mov_b32_e32 v50, s1
	s_nop 0
	v_add_f32_e32 v50, s0, v50
	v_cndmask_b32_e64 v50, v51, v50, s[8:9]
	v_mul_f32_e32 v50, 0x3b800000, v50
	v_pk_add_f32 v[46:47], v[46:47], v[50:51] op_sel_hi:[1,0] neg_lo:[0,1] neg_hi:[0,1]
	v_pk_add_f32 v[52:53], v[52:53], v[50:51] op_sel_hi:[1,0] neg_lo:[0,1] neg_hi:[0,1]
	v_pk_mul_f32 v[86:87], v[46:47], v[46:47]
	v_pk_mul_f32 v[88:89], v[52:53], v[52:53]
	v_add_f32_e32 v86, v86, v87
	v_pk_add_f32 v[48:49], v[48:49], v[50:51] op_sel_hi:[1,0] neg_lo:[0,1] neg_hi:[0,1]
	v_add_f32_e32 v86, v88, v86
	v_pk_mul_f32 v[100:101], v[48:49], v[48:49]
	v_add_f32_e32 v86, v89, v86
	v_pk_add_f32 v[50:51], v[82:83], v[50:51] op_sel_hi:[1,0] neg_lo:[0,1] neg_hi:[0,1]
	v_add_f32_e32 v86, v100, v86
	v_pk_mul_f32 v[82:83], v[50:51], v[50:51]
	v_add_f32_e32 v86, v101, v86
	v_add_f32_e32 v82, v82, v86
	v_add_f32_e32 v82, v83, v82
	s_nop 1
	v_add_f32_dpp v82, v82, v82 quad_perm:[1,0,3,2] row_mask:0xf bank_mask:0xf bound_ctrl:1
	s_nop 1
	v_add_f32_dpp v82, v82, v82 quad_perm:[2,3,0,1] row_mask:0xf bank_mask:0xf bound_ctrl:1
	s_nop 1
	v_add_f32_dpp v82, v82, v82 row_half_mirror row_mask:0xf bank_mask:0xf bound_ctrl:1
	s_nop 1
	v_add_f32_dpp v82, v82, v82 row_mirror row_mask:0xf bank_mask:0xf bound_ctrl:1
	s_nop 0
	v_readlane_b32 s1, v82, 16
	v_readlane_b32 s0, v82, 0
	s_nop 0
	v_mov_b32_e32 v83, s1
	v_readlane_b32 s1, v82, 48
	v_add_f32_e32 v83, s0, v83
	v_readlane_b32 s0, v82, 32
	v_mov_b32_e32 v82, s1
	s_nop 0
	v_add_f32_e32 v82, s0, v82
	v_cndmask_b32_e64 v82, v83, v82, s[8:9]
	v_fmamk_f32 v82, v82, 0x3b800000, v103
	v_cmp_gt_f32_e32 vcc, s6, v82
	v_mul_f32_e32 v83, 0x4f800000, v82
	s_nop 0
	v_cndmask_b32_e32 v82, v82, v83, vcc
	v_sqrt_f32_e32 v83, v82
	s_nop 0
	v_add_u32_e32 v86, -1, v83
	v_fma_f32 v87, -v86, v83, v82
	v_cmp_ge_f32_e64 s[12:13], 0, v87
	v_add_u32_e32 v87, 1, v83
	s_nop 0
	v_cndmask_b32_e64 v86, v83, v86, s[12:13]
	v_fma_f32 v83, -v87, v83, v82
	v_cmp_lt_f32_e64 s[12:13], 0, v83
	s_nop 1
	v_cndmask_b32_e64 v83, v86, v87, s[12:13]
	v_mul_f32_e32 v86, 0x37800000, v83
	v_cndmask_b32_e32 v83, v83, v86, vcc
	v_cmp_class_f32_e32 vcc, v82, v104
	s_nop 1
	v_cndmask_b32_e32 v82, v83, v82, vcc
	v_div_scale_f32 v83, s[0:1], v82, v82, 1.0
	v_rcp_f32_e32 v86, v83
	s_nop 0
	v_fma_f32 v87, -v83, v86, 1.0
	v_fmac_f32_e32 v86, v87, v86
	v_div_scale_f32 v87, vcc, 1.0, v82, 1.0
	v_mul_f32_e32 v88, v87, v86
	v_fma_f32 v89, -v83, v88, v87
	v_fmac_f32_e32 v88, v89, v86
	v_fma_f32 v83, -v83, v88, v87
	v_div_fmas_f32 v83, v83, v86, v88
	v_div_fixup_f32 v82, v83, v82, 1.0
	v_pk_mul_f32 v[46:47], v[46:47], v[82:83] op_sel_hi:[1,0]
	v_pk_mul_f32 v[48:49], v[48:49], v[82:83] op_sel_hi:[1,0]
	v_pk_mul_f32 v[46:47], v[10:11], v[46:47]
	v_pk_mul_f32 v[48:49], v[14:15], v[48:49]
	v_pk_mul_f32 v[42:43], v[42:43], v[46:47]
	v_pk_mul_f32 v[46:47], v[52:53], v[82:83] op_sel_hi:[1,0]
	v_pk_mul_f32 v[44:45], v[44:45], v[48:49]
	v_pk_mul_f32 v[48:49], v[50:51], v[82:83] op_sel_hi:[1,0]
	v_pk_mul_f32 v[46:47], v[12:13], v[46:47]
	v_pk_mul_f32 v[48:49], v[16:17], v[48:49]
	v_pk_mul_f32 v[46:47], v[84:85], v[46:47]
	v_pk_mul_f32 v[48:49], v[80:81], v[48:49]
	v_cvt_pk_bf16_f32 v42, v42, v43
	v_cvt_pk_bf16_f32 v43, v46, v47
	v_cvt_pk_bf16_f32 v44, v44, v45
	v_cvt_pk_bf16_f32 v45, v48, v49
	global_store_dwordx4 v[78:79], v[42:45], off offset:1024
	v_mov_b64_e32 v[80:81], v[20:21]
	v_mov_b64_e32 v[78:79], v[18:19]
	v_mov_b64_e32 v[44:45], v[24:25]
	v_mov_b64_e32 v[42:43], v[22:23]
	s_waitcnt vmcnt(0) lgkmcnt(0)
	v_mov_b64_e32 v[22:23], v[74:75]
	v_mov_b64_e32 v[18:19], v[70:71]
	v_mov_b64_e32 v[84:85], v[68:69]
	v_mov_b64_e32 v[46:47], v[62:63]
	v_mov_b64_e32 v[88:89], v[60:61]
	v_mov_b64_e32 v[50:51], v[54:55]
	v_mov_b64_e32 v[24:25], v[76:77]
	v_mov_b64_e32 v[20:21], v[72:73]
	v_mov_b64_e32 v[82:83], v[66:67]
	v_mov_b64_e32 v[48:49], v[64:65]
	v_mov_b64_e32 v[86:87], v[58:59]
	v_mov_b64_e32 v[52:53], v[56:57]
	s_cbranch_scc1 .LBB0_1040
	s_add_i32 s7, s7, s74
	s_add_i32 s4, s4, s5
	s_cmpk_gt_i32 s7, 0xff
	s_cbranch_scc0 .LBB0_1039

.LBB0_1047:
	ds_read_b128 v[130:133], v170
	ds_read_b128 v[134:137], v170 offset:1024
	ds_read_b128 v[138:141], v170 offset:2048
	ds_read_b128 v[142:145], v170 offset:3072
	s_add_u32 s0, s38, 0xfffc0080
	s_addc_u32 s1, s39, -1
	s_cmp_eq_u32 s69, 12
	s_cselect_b32 s43, s60, s1
	s_cselect_b32 s42, s61, s0
	s_cselect_b32 s41, s62, s65
	s_cselect_b32 s40, s63, s64
	s_mov_b32 m0, s50
	v_lshl_add_u64 v[166:167], s[38:39], 0, v[164:165]
	ds_read_b128 v[146:149], v171
	ds_read_b128 v[174:177], v171 offset:1024
	ds_read_b128 v[178:181], v171 offset:2048
	ds_read_b128 v[182:185], v171 offset:3072
	ds_read_b128 v[186:189], v171 offset:4096
	ds_read_b128 v[190:193], v171 offset:5120
	ds_read_b128 v[194:197], v171 offset:6144
	ds_read_b128 v[198:201], v171 offset:7168
	global_load_lds_dwordx4 v[166:167], off
	v_lshl_add_u64 v[166:167], s[38:39], 0, v[162:163]
	s_mov_b32 m0, s51
	s_nop 0
	global_load_lds_dwordx4 v[166:167], off
	s_waitcnt lgkmcnt(8)
	s_waitcnt vmcnt(10)
	s_barrier
	s_waitcnt lgkmcnt(0)
	s_waitcnt lgkmcnt(0)
	v_mfma_f32_16x16x32_bf16 v[126:129], v[130:133], v[146:149], v[126:129]
	v_mfma_f32_16x16x32_bf16 v[122:125], v[138:141], v[146:149], v[122:125]
	v_mfma_f32_16x16x32_bf16 v[118:121], v[130:133], v[178:181], v[118:121]
	v_mfma_f32_16x16x32_bf16 v[110:113], v[138:141], v[178:181], v[110:113]
	v_mfma_f32_16x16x32_bf16 v[98:101], v[130:133], v[186:189], v[98:101]
	v_mfma_f32_16x16x32_bf16 v[90:93], v[138:141], v[186:189], v[90:93]
	v_mfma_f32_16x16x32_bf16 v[82:85], v[130:133], v[194:197], v[82:85]
	v_mfma_f32_16x16x32_bf16 v[74:77], v[138:141], v[194:197], v[74:77]
	v_mfma_f32_16x16x32_bf16 v[126:129], v[134:137], v[174:177], v[126:129]
	v_mfma_f32_16x16x32_bf16 v[122:125], v[142:145], v[174:177], v[122:125]
	v_mfma_f32_16x16x32_bf16 v[118:121], v[134:137], v[182:185], v[118:121]
	v_mfma_f32_16x16x32_bf16 v[110:113], v[142:145], v[182:185], v[110:113]
	v_mfma_f32_16x16x32_bf16 v[98:101], v[134:137], v[190:193], v[98:101]
	v_mfma_f32_16x16x32_bf16 v[90:93], v[142:145], v[190:193], v[90:93]
	v_mfma_f32_16x16x32_bf16 v[82:85], v[134:137], v[198:201], v[82:85]
	v_mfma_f32_16x16x32_bf16 v[74:77], v[142:145], v[198:201], v[74:77]
	s_barrier
	s_mov_b32 m0, s52
	v_lshl_add_u64 v[166:167], s[40:41], 0, v[158:159]
	ds_read_b128 v[202:205], v172
	ds_read_b128 v[206:209], v172 offset:1024
	ds_read_b128 v[210:213], v172 offset:2048
	ds_read_b128 v[214:217], v172 offset:3072
	global_load_lds_dwordx4 v[166:167], off
	v_lshl_add_u64 v[218:219], s[40:41], 0, v[154:155]
	s_mov_b32 m0, s53
	s_nop 0
	global_load_lds_dwordx4 v[218:219], off
	s_waitcnt vmcnt(10)
	s_barrier
	s_waitcnt lgkmcnt(0)
	s_waitcnt lgkmcnt(0)
	v_mfma_f32_16x16x32_bf16 v[114:117], v[202:205], v[146:149], v[114:117]
	v_mfma_f32_16x16x32_bf16 v[106:109], v[210:213], v[146:149], v[106:109]
	v_mfma_f32_16x16x32_bf16 v[102:105], v[202:205], v[178:181], v[102:105]
	v_mfma_f32_16x16x32_bf16 v[94:97], v[210:213], v[178:181], v[94:97]
	v_mfma_f32_16x16x32_bf16 v[86:89], v[202:205], v[186:189], v[86:89]
	v_mfma_f32_16x16x32_bf16 v[78:81], v[210:213], v[186:189], v[78:81]
	v_mfma_f32_16x16x32_bf16 v[70:73], v[202:205], v[194:197], v[70:73]
	v_mfma_f32_16x16x32_bf16 v[66:69], v[210:213], v[194:197], v[66:69]
	v_mfma_f32_16x16x32_bf16 v[114:117], v[206:209], v[174:177], v[114:117]
	v_mfma_f32_16x16x32_bf16 v[106:109], v[214:217], v[174:177], v[106:109]
	v_mfma_f32_16x16x32_bf16 v[102:105], v[206:209], v[182:185], v[102:105]
	v_mfma_f32_16x16x32_bf16 v[94:97], v[214:217], v[182:185], v[94:97]
	v_mfma_f32_16x16x32_bf16 v[86:89], v[206:209], v[190:193], v[86:89]
	v_mfma_f32_16x16x32_bf16 v[78:81], v[214:217], v[190:193], v[78:81]
	v_mfma_f32_16x16x32_bf16 v[70:73], v[206:209], v[198:201], v[70:73]
	v_mfma_f32_16x16x32_bf16 v[66:69], v[214:217], v[198:201], v[66:69]
	s_mov_b32 m0, s6
	v_lshl_add_u64 v[220:221], s[42:43], 0, v[160:161]
	s_barrier
	ds_read_b128 v[146:149], v171 offset:16384
	ds_read_b128 v[174:177], v171 offset:17408
	ds_read_b128 v[178:181], v171 offset:18432
	ds_read_b128 v[182:185], v171 offset:19456
	ds_read_b128 v[186:189], v171 offset:20480
	ds_read_b128 v[190:193], v171 offset:21504
	ds_read_b128 v[194:197], v171 offset:22528
	ds_read_b128 v[198:201], v171 offset:23552
	global_load_lds_dwordx4 v[220:221], off
	v_lshl_add_u64 v[222:223], s[42:43], 0, v[156:157]
	s_mov_b32 m0, s7
	s_nop 0
	global_load_lds_dwordx4 v[222:223], off
	s_waitcnt vmcnt(10)
	s_barrier
	s_waitcnt lgkmcnt(0)
	s_waitcnt lgkmcnt(0)
	v_mfma_f32_16x16x32_bf16 v[62:65], v[130:133], v[146:149], v[62:65]
	v_mfma_f32_16x16x32_bf16 v[58:61], v[138:141], v[146:149], v[58:61]
	v_mfma_f32_16x16x32_bf16 v[50:53], v[130:133], v[178:181], v[50:53]
	v_mfma_f32_16x16x32_bf16 v[42:45], v[138:141], v[178:181], v[42:45]
	v_mfma_f32_16x16x32_bf16 v[34:37], v[130:133], v[186:189], v[34:37]
	v_mfma_f32_16x16x32_bf16 v[26:29], v[138:141], v[186:189], v[26:29]
	v_mfma_f32_16x16x32_bf16 v[18:21], v[130:133], v[194:197], v[18:21]
	v_mfma_f32_16x16x32_bf16 v[10:13], v[138:141], v[194:197], v[10:13]
	v_mfma_f32_16x16x32_bf16 v[62:65], v[134:137], v[174:177], v[62:65]
	v_mfma_f32_16x16x32_bf16 v[58:61], v[142:145], v[174:177], v[58:61]
	v_mfma_f32_16x16x32_bf16 v[50:53], v[134:137], v[182:185], v[50:53]
	v_mfma_f32_16x16x32_bf16 v[42:45], v[142:145], v[182:185], v[42:45]
	v_mfma_f32_16x16x32_bf16 v[34:37], v[134:137], v[190:193], v[34:37]
	v_mfma_f32_16x16x32_bf16 v[26:29], v[142:145], v[190:193], v[26:29]
	v_mfma_f32_16x16x32_bf16 v[18:21], v[134:137], v[198:201], v[18:21]
	v_mfma_f32_16x16x32_bf16 v[10:13], v[142:145], v[198:201], v[10:13]
	s_barrier
	s_add_u32 s0, s40, 0x40000
	s_addc_u32 s1, s41, 0
	s_mov_b32 m0, s54
	v_lshl_add_u64 v[130:131], s[0:1], 0, v[158:159]
	global_load_lds_dwordx4 v[130:131], off
	v_lshl_add_u64 v[130:131], s[0:1], 0, v[154:155]
	s_add_i32 m0, s54, 0x2000
	s_nop 0
	global_load_lds_dwordx4 v[130:131], off
	s_waitcnt vmcnt(10)
	s_barrier
	v_mfma_f32_16x16x32_bf16 v[54:57], v[202:205], v[146:149], v[54:57]
	v_mfma_f32_16x16x32_bf16 v[46:49], v[210:213], v[146:149], v[46:49]
	v_mfma_f32_16x16x32_bf16 v[38:41], v[202:205], v[178:181], v[38:41]
	v_mfma_f32_16x16x32_bf16 v[30:33], v[210:213], v[178:181], v[30:33]
	v_mfma_f32_16x16x32_bf16 v[22:25], v[202:205], v[186:189], v[22:25]
	v_mfma_f32_16x16x32_bf16 v[14:17], v[210:213], v[186:189], v[14:17]
	v_mfma_f32_16x16x32_bf16 v[6:9], v[202:205], v[194:197], v[6:9]
	v_mfma_f32_16x16x32_bf16 v[2:5], v[210:213], v[194:197], v[2:5]
	v_mfma_f32_16x16x32_bf16 v[54:57], v[206:209], v[174:177], v[54:57]
	v_mfma_f32_16x16x32_bf16 v[46:49], v[214:217], v[174:177], v[46:49]
	v_mfma_f32_16x16x32_bf16 v[38:41], v[206:209], v[182:185], v[38:41]
	v_mfma_f32_16x16x32_bf16 v[30:33], v[214:217], v[182:185], v[30:33]
	v_mfma_f32_16x16x32_bf16 v[22:25], v[206:209], v[190:193], v[22:25]
	v_mfma_f32_16x16x32_bf16 v[14:17], v[214:217], v[190:193], v[14:17]
	v_mfma_f32_16x16x32_bf16 v[6:9], v[206:209], v[198:201], v[6:9]
	v_mfma_f32_16x16x32_bf16 v[2:5], v[214:217], v[198:201], v[2:5]
	s_add_i32 s70, 0, 0x18000
	v_add_u32_e32 v142, s70, v169
	s_barrier
	ds_read_b128 v[130:133], v142
	ds_read_b128 v[134:137], v142 offset:1024
	ds_read_b128 v[138:141], v142 offset:2048
	ds_read_b128 v[142:145], v142 offset:3072
	s_add_u32 s0, s42, 0x40000
	s_addc_u32 s1, s43, 0
	s_mov_b32 m0, s10
	v_lshl_add_u64 v[202:203], s[0:1], 0, v[160:161]
	ds_read_b128 v[146:149], v171 offset:32768
	ds_read_b128 v[174:177], v171 offset:33792
	ds_read_b128 v[178:181], v171 offset:34816
	ds_read_b128 v[182:185], v171 offset:35840
	ds_read_b128 v[186:189], v171 offset:36864
	ds_read_b128 v[190:193], v171 offset:37888
	ds_read_b128 v[194:197], v171 offset:38912
	ds_read_b128 v[198:201], v171 offset:39936
	global_load_lds_dwordx4 v[202:203], off
	v_lshl_add_u64 v[202:203], s[0:1], 0, v[156:157]
	s_mov_b32 m0, s11
	s_nop 0
	global_load_lds_dwordx4 v[202:203], off
	s_waitcnt lgkmcnt(8)
	s_waitcnt vmcnt(10)
	s_barrier
	s_waitcnt lgkmcnt(0)
	s_waitcnt lgkmcnt(0)
	v_mfma_f32_16x16x32_bf16 v[126:129], v[130:133], v[146:149], v[126:129]
	v_mfma_f32_16x16x32_bf16 v[122:125], v[138:141], v[146:149], v[122:125]
	v_mfma_f32_16x16x32_bf16 v[118:121], v[130:133], v[178:181], v[118:121]
	v_mfma_f32_16x16x32_bf16 v[110:113], v[138:141], v[178:181], v[110:113]
	v_mfma_f32_16x16x32_bf16 v[98:101], v[130:133], v[186:189], v[98:101]
	v_mfma_f32_16x16x32_bf16 v[90:93], v[138:141], v[186:189], v[90:93]
	v_mfma_f32_16x16x32_bf16 v[82:85], v[130:133], v[194:197], v[82:85]
	v_mfma_f32_16x16x32_bf16 v[74:77], v[138:141], v[194:197], v[74:77]
	v_mfma_f32_16x16x32_bf16 v[126:129], v[134:137], v[174:177], v[126:129]
	v_mfma_f32_16x16x32_bf16 v[122:125], v[142:145], v[174:177], v[122:125]
	v_mfma_f32_16x16x32_bf16 v[118:121], v[134:137], v[182:185], v[118:121]
	v_mfma_f32_16x16x32_bf16 v[110:113], v[142:145], v[182:185], v[110:113]
	v_mfma_f32_16x16x32_bf16 v[98:101], v[134:137], v[190:193], v[98:101]
	v_mfma_f32_16x16x32_bf16 v[90:93], v[142:145], v[190:193], v[90:93]
	v_mfma_f32_16x16x32_bf16 v[82:85], v[134:137], v[198:201], v[82:85]
	v_mfma_f32_16x16x32_bf16 v[74:77], v[142:145], v[198:201], v[74:77]
	s_barrier
	s_add_i32 s42, 0, 0x1c000
	s_add_i32 s0, s70, s5
	v_add_u32_e32 v173, s42, v169
	v_lshl_add_u64 v[166:167], v[166:167], 0, s[28:29]
	s_mov_b32 m0, s0
	ds_read_b128 v[202:205], v173
	ds_read_b128 v[206:209], v173 offset:1024
	ds_read_b128 v[210:213], v173 offset:2048
	ds_read_b128 v[214:217], v173 offset:3072
	global_load_lds_dwordx4 v[166:167], off
	v_lshl_add_u64 v[166:167], v[218:219], 0, s[28:29]
	s_add_i32 m0, s0, 0x2000
	s_nop 0
	global_load_lds_dwordx4 v[166:167], off
	s_waitcnt vmcnt(10)
	s_barrier
	s_waitcnt lgkmcnt(0)
	s_waitcnt lgkmcnt(0)
	v_mfma_f32_16x16x32_bf16 v[114:117], v[202:205], v[146:149], v[114:117]
	v_mfma_f32_16x16x32_bf16 v[106:109], v[210:213], v[146:149], v[106:109]
	v_mfma_f32_16x16x32_bf16 v[102:105], v[202:205], v[178:181], v[102:105]
	v_mfma_f32_16x16x32_bf16 v[94:97], v[210:213], v[178:181], v[94:97]
	v_mfma_f32_16x16x32_bf16 v[86:89], v[202:205], v[186:189], v[86:89]
	v_mfma_f32_16x16x32_bf16 v[78:81], v[210:213], v[186:189], v[78:81]
	v_mfma_f32_16x16x32_bf16 v[70:73], v[202:205], v[194:197], v[70:73]
	v_mfma_f32_16x16x32_bf16 v[66:69], v[210:213], v[194:197], v[66:69]
	v_mfma_f32_16x16x32_bf16 v[114:117], v[206:209], v[174:177], v[114:117]
	v_mfma_f32_16x16x32_bf16 v[106:109], v[214:217], v[174:177], v[106:109]
	v_mfma_f32_16x16x32_bf16 v[102:105], v[206:209], v[182:185], v[102:105]
	v_mfma_f32_16x16x32_bf16 v[94:97], v[214:217], v[182:185], v[94:97]
	v_mfma_f32_16x16x32_bf16 v[86:89], v[206:209], v[190:193], v[86:89]
	v_mfma_f32_16x16x32_bf16 v[78:81], v[214:217], v[190:193], v[78:81]
	v_mfma_f32_16x16x32_bf16 v[70:73], v[206:209], v[198:201], v[70:73]
	v_mfma_f32_16x16x32_bf16 v[66:69], v[214:217], v[198:201], v[66:69]
	s_mov_b32 m0, s48
	v_lshl_add_u64 v[166:167], v[220:221], 0, s[28:29]
	s_barrier
	ds_read_b128 v[146:149], v171 offset:49152
	ds_read_b128 v[174:177], v171 offset:50176
	ds_read_b128 v[178:181], v171 offset:51200
	ds_read_b128 v[182:185], v171 offset:52224
	ds_read_b128 v[186:189], v171 offset:53248
	ds_read_b128 v[190:193], v171 offset:54272
	ds_read_b128 v[194:197], v171 offset:55296
	ds_read_b128 v[198:201], v171 offset:56320
	global_load_lds_dwordx4 v[166:167], off
	v_lshl_add_u64 v[166:167], v[222:223], 0, s[28:29]
	s_mov_b32 m0, s49
	s_nop 0
	global_load_lds_dwordx4 v[166:167], off
	s_waitcnt vmcnt(10)
	s_barrier
	s_waitcnt lgkmcnt(0)
	s_waitcnt lgkmcnt(0)
	v_mfma_f32_16x16x32_bf16 v[62:65], v[130:133], v[146:149], v[62:65]
	v_mfma_f32_16x16x32_bf16 v[58:61], v[138:141], v[146:149], v[58:61]
	v_mfma_f32_16x16x32_bf16 v[50:53], v[130:133], v[178:181], v[50:53]
	v_mfma_f32_16x16x32_bf16 v[42:45], v[138:141], v[178:181], v[42:45]
	v_mfma_f32_16x16x32_bf16 v[34:37], v[130:133], v[186:189], v[34:37]
	v_mfma_f32_16x16x32_bf16 v[26:29], v[138:141], v[186:189], v[26:29]
	v_mfma_f32_16x16x32_bf16 v[18:21], v[130:133], v[194:197], v[18:21]
	v_mfma_f32_16x16x32_bf16 v[10:13], v[138:141], v[194:197], v[10:13]
	v_mfma_f32_16x16x32_bf16 v[62:65], v[134:137], v[174:177], v[62:65]
	v_mfma_f32_16x16x32_bf16 v[58:61], v[142:145], v[174:177], v[58:61]
	v_mfma_f32_16x16x32_bf16 v[50:53], v[134:137], v[182:185], v[50:53]
	v_mfma_f32_16x16x32_bf16 v[42:45], v[142:145], v[182:185], v[42:45]
	v_mfma_f32_16x16x32_bf16 v[34:37], v[134:137], v[190:193], v[34:37]
	v_mfma_f32_16x16x32_bf16 v[26:29], v[142:145], v[190:193], v[26:29]
	v_mfma_f32_16x16x32_bf16 v[18:21], v[134:137], v[198:201], v[18:21]
	v_mfma_f32_16x16x32_bf16 v[10:13], v[142:145], v[198:201], v[10:13]
	s_barrier
	s_add_u32 s0, s40, 0x40080
	s_addc_u32 s1, s41, 0
	s_add_i32 s40, s42, s5
	v_lshl_add_u64 v[130:131], s[0:1], 0, v[158:159]
	s_mov_b32 m0, s40
	s_nop 0
	global_load_lds_dwordx4 v[130:131], off
	v_lshl_add_u64 v[130:131], s[0:1], 0, v[154:155]
	s_add_i32 m0, s40, 0x2000
	s_nop 0
	global_load_lds_dwordx4 v[130:131], off
	s_waitcnt vmcnt(10)
	s_barrier
	v_mfma_f32_16x16x32_bf16 v[54:57], v[202:205], v[146:149], v[54:57]
	v_mfma_f32_16x16x32_bf16 v[46:49], v[210:213], v[146:149], v[46:49]
	v_mfma_f32_16x16x32_bf16 v[38:41], v[202:205], v[178:181], v[38:41]
	v_mfma_f32_16x16x32_bf16 v[30:33], v[210:213], v[178:181], v[30:33]
	v_mfma_f32_16x16x32_bf16 v[22:25], v[202:205], v[186:189], v[22:25]
	v_mfma_f32_16x16x32_bf16 v[14:17], v[210:213], v[186:189], v[14:17]
	v_mfma_f32_16x16x32_bf16 v[6:9], v[202:205], v[194:197], v[6:9]
	v_mfma_f32_16x16x32_bf16 v[2:5], v[210:213], v[194:197], v[2:5]
	v_mfma_f32_16x16x32_bf16 v[54:57], v[206:209], v[174:177], v[54:57]
	v_mfma_f32_16x16x32_bf16 v[46:49], v[214:217], v[174:177], v[46:49]
	v_mfma_f32_16x16x32_bf16 v[38:41], v[206:209], v[182:185], v[38:41]
	v_mfma_f32_16x16x32_bf16 v[30:33], v[214:217], v[182:185], v[30:33]
	v_mfma_f32_16x16x32_bf16 v[22:25], v[206:209], v[190:193], v[22:25]
	v_mfma_f32_16x16x32_bf16 v[14:17], v[214:217], v[190:193], v[14:17]
	v_mfma_f32_16x16x32_bf16 v[6:9], v[206:209], v[198:201], v[6:9]
	v_mfma_f32_16x16x32_bf16 v[2:5], v[214:217], v[198:201], v[2:5]
	s_add_i32 s69, s69, 2
	s_add_u32 s64, s64, 0x100
	s_addc_u32 s65, s65, 0
	s_add_u32 s38, s38, 0x100
	s_addc_u32 s39, s39, 0
	s_cmp_gt_u32 s69, 13
	s_barrier
	s_cbranch_scc0 .LBB0_1047
	s_lshl_b32 s0, s58, 8
	v_mov_b32_e32 v130, v151
	v_mov_b32_e32 v131, v153
	s_or_b32 s0, s0, s45
	s_mov_b32 s58, s57
	v_lshl_add_u32 v166, v131, 3, s0
	s_lshl_b32 s0, s59, 8
	s_add_i32 s0, s0, s44
	v_add_u32_e32 v173, s0, v130
	v_mov_b32_e32 v130, v173
	v_ashrrev_i32_e32 v167, 31, v166
	v_ashrrev_i32_e32 v131, 31, v130
	v_lshlrev_b64 v[130:131], 10, v[130:131]
	v_lshl_add_u64 v[130:131], v[130:131], 0, v[166:167]
	v_lshlrev_b64 v[186:187], 1, v[130:131]
	v_lshl_add_u64 v[130:131], s[12:13], 0, v[186:187]
	global_load_dwordx4 v[174:177], v[130:131], off
	global_load_dwordx4 v[178:181], v[130:131], off offset:256
	v_add_co_u32_e32 v132, vcc, s47, v130
	s_mov_b32 s59, s56
	s_nop 0
	v_addc_co_u32_e32 v133, vcc, 0, v131, vcc
	global_load_dwordx4 v[182:185], v[132:133], off
	global_load_dwordx4 v[146:149], v[132:133], off offset:256
	v_add_co_u32_e32 v132, vcc, s31, v130
	s_waitcnt vmcnt(0) lgkmcnt(0)
	v_lshlrev_b32_e32 v188, 16, v174
	v_addc_co_u32_e32 v133, vcc, 0, v131, vcc
	global_load_dwordx4 v[142:145], v[132:133], off
	global_load_dwordx4 v[138:141], v[132:133], off offset:256
	v_add_co_u32_e32 v130, vcc, s46, v130
	v_and_b32_e32 v189, 0xffff0000, v174
	s_nop 0
	v_addc_co_u32_e32 v131, vcc, 0, v131, vcc
	global_load_dwordx4 v[134:137], v[130:131], off
	s_nop 0
	global_load_dwordx4 v[130:133], v[130:131], off offset:256
	v_lshlrev_b32_e32 v174, 16, v175
	v_and_b32_e32 v175, 0xffff0000, v175
	v_lshlrev_b32_e32 v190, 16, v176
	v_and_b32_e32 v191, 0xffff0000, v176
	v_lshlrev_b32_e32 v176, 16, v177
	v_and_b32_e32 v177, 0xffff0000, v177
	v_pk_fma_f32 v[128:129], v[174:175], s[30:31], v[128:129] op_sel_hi:[1,0,1]
	v_pk_fma_f32 v[126:127], v[188:189], s[30:31], v[126:127] op_sel_hi:[1,0,1]
	v_pk_fma_f32 v[174:175], v[176:177], s[30:31], v[124:125] op_sel_hi:[1,0,1]
	v_pk_fma_f32 v[122:123], v[190:191], s[30:31], v[122:123] op_sel_hi:[1,0,1]
	v_cvt_pk_bf16_f32 v124, v126, v127
	v_cvt_pk_bf16_f32 v125, v128, v129
	v_cvt_pk_bf16_f32 v126, v122, v123
	v_cvt_pk_bf16_f32 v127, v174, v175
	v_lshl_add_u64 v[122:123], s[24:25], 0, v[186:187]
	global_store_dwordx4 v[122:123], v[124:127], off
	v_lshlrev_b32_e32 v128, 16, v180
	v_and_b32_e32 v129, 0xffff0000, v180
	v_lshlrev_b32_e32 v124, 16, v178
	v_and_b32_e32 v125, 0xffff0000, v178
	v_lshlrev_b32_e32 v126, 16, v179
	v_and_b32_e32 v127, 0xffff0000, v179
	v_lshlrev_b32_e32 v174, 16, v181
	v_and_b32_e32 v175, 0xffff0000, v181
	v_pk_fma_f32 v[116:117], v[126:127], s[30:31], v[116:117] op_sel_hi:[1,0,1]
	v_pk_fma_f32 v[114:115], v[124:125], s[30:31], v[114:115] op_sel_hi:[1,0,1]
	v_pk_fma_f32 v[124:125], v[174:175], s[30:31], v[108:109] op_sel_hi:[1,0,1]
	v_pk_fma_f32 v[108:109], v[128:129], s[30:31], v[106:107] op_sel_hi:[1,0,1]
	v_cvt_pk_bf16_f32 v106, v114, v115
	v_cvt_pk_bf16_f32 v107, v116, v117
	v_cvt_pk_bf16_f32 v108, v108, v109
	v_cvt_pk_bf16_f32 v109, v124, v125
	global_store_dwordx4 v[122:123], v[106:109], off offset:256
	v_lshlrev_b32_e32 v114, 16, v184
	v_and_b32_e32 v115, 0xffff0000, v184
	v_lshlrev_b32_e32 v106, 16, v182
	v_and_b32_e32 v107, 0xffff0000, v182
	v_lshlrev_b32_e32 v108, 16, v183
	v_and_b32_e32 v109, 0xffff0000, v183
	v_lshlrev_b32_e32 v116, 16, v185
	v_and_b32_e32 v117, 0xffff0000, v185
	v_pk_fma_f32 v[108:109], v[108:109], s[30:31], v[120:121] op_sel_hi:[1,0,1]
	v_pk_fma_f32 v[106:107], v[106:107], s[30:31], v[118:119] op_sel_hi:[1,0,1]
	v_pk_fma_f32 v[110:111], v[114:115], s[30:31], v[110:111] op_sel_hi:[1,0,1]
	v_pk_fma_f32 v[112:113], v[116:117], s[30:31], v[112:113] op_sel_hi:[1,0,1]
	v_cvt_pk_bf16_f32 v106, v106, v107
	v_cvt_pk_bf16_f32 v107, v108, v109
	v_cvt_pk_bf16_f32 v108, v110, v111
	v_add_co_u32_e32 v110, vcc, s47, v122
	v_cvt_pk_bf16_f32 v109, v112, v113
	s_nop 0
	v_addc_co_u32_e32 v111, vcc, 0, v123, vcc
	global_store_dwordx4 v[110:111], v[106:109], off
	v_lshlrev_b32_e32 v112, 16, v148
	v_and_b32_e32 v113, 0xffff0000, v148
	v_lshlrev_b32_e32 v106, 16, v146
	v_and_b32_e32 v107, 0xffff0000, v146
	v_lshlrev_b32_e32 v108, 16, v147
	v_and_b32_e32 v109, 0xffff0000, v147
	v_lshlrev_b32_e32 v114, 16, v149
	v_and_b32_e32 v115, 0xffff0000, v149
	v_pk_fma_f32 v[104:105], v[108:109], s[30:31], v[104:105] op_sel_hi:[1,0,1]
	v_pk_fma_f32 v[102:103], v[106:107], s[30:31], v[102:103] op_sel_hi:[1,0,1]
	v_pk_fma_f32 v[106:107], v[114:115], s[30:31], v[96:97] op_sel_hi:[1,0,1]
	v_pk_fma_f32 v[96:97], v[112:113], s[30:31], v[94:95] op_sel_hi:[1,0,1]
	v_cvt_pk_bf16_f32 v94, v102, v103
	v_cvt_pk_bf16_f32 v95, v104, v105
	v_cvt_pk_bf16_f32 v96, v96, v97
	v_cvt_pk_bf16_f32 v97, v106, v107
	global_store_dwordx4 v[110:111], v[94:97], off offset:256
	s_waitcnt vmcnt(0) lgkmcnt(0)
	v_lshlrev_b32_e32 v102, 16, v144
	v_lshlrev_b32_e32 v94, 16, v142
	v_and_b32_e32 v95, 0xffff0000, v142
	v_lshlrev_b32_e32 v96, 16, v143
	v_and_b32_e32 v97, 0xffff0000, v143
	v_and_b32_e32 v103, 0xffff0000, v144
	v_lshlrev_b32_e32 v104, 16, v145
	v_and_b32_e32 v105, 0xffff0000, v145
	v_pk_fma_f32 v[94:95], v[94:95], s[30:31], v[98:99] op_sel_hi:[1,0,1]
	v_pk_fma_f32 v[96:97], v[96:97], s[30:31], v[100:101] op_sel_hi:[1,0,1]
	v_pk_fma_f32 v[98:99], v[104:105], s[30:31], v[92:93] op_sel_hi:[1,0,1]
	v_pk_fma_f32 v[92:93], v[102:103], s[30:31], v[90:91] op_sel_hi:[1,0,1]
	v_cvt_pk_bf16_f32 v90, v94, v95
	v_add_co_u32_e32 v94, vcc, s31, v122
	v_cvt_pk_bf16_f32 v91, v96, v97
	v_cvt_pk_bf16_f32 v92, v92, v93
	v_cvt_pk_bf16_f32 v93, v98, v99
	v_addc_co_u32_e32 v95, vcc, 0, v123, vcc
	global_store_dwordx4 v[94:95], v[90:93], off
	v_lshlrev_b32_e32 v96, 16, v140
	v_and_b32_e32 v97, 0xffff0000, v140
	v_lshlrev_b32_e32 v90, 16, v138
	v_and_b32_e32 v91, 0xffff0000, v138
	v_lshlrev_b32_e32 v92, 16, v139
	v_and_b32_e32 v93, 0xffff0000, v139
	v_lshlrev_b32_e32 v98, 16, v141
	v_and_b32_e32 v99, 0xffff0000, v141
	v_pk_fma_f32 v[88:89], v[92:93], s[30:31], v[88:89] op_sel_hi:[1,0,1]
	v_pk_fma_f32 v[86:87], v[90:91], s[30:31], v[86:87] op_sel_hi:[1,0,1]
	v_pk_fma_f32 v[90:91], v[98:99], s[30:31], v[80:81] op_sel_hi:[1,0,1]
	v_pk_fma_f32 v[80:81], v[96:97], s[30:31], v[78:79] op_sel_hi:[1,0,1]
	v_cvt_pk_bf16_f32 v78, v86, v87
	v_cvt_pk_bf16_f32 v79, v88, v89
	v_cvt_pk_bf16_f32 v80, v80, v81
	v_cvt_pk_bf16_f32 v81, v90, v91
	global_store_dwordx4 v[94:95], v[78:81], off offset:256
	v_lshlrev_b32_e32 v86, 16, v136
	v_and_b32_e32 v87, 0xffff0000, v136
	v_lshlrev_b32_e32 v78, 16, v134
	v_and_b32_e32 v79, 0xffff0000, v134
	v_lshlrev_b32_e32 v80, 16, v135
	v_and_b32_e32 v81, 0xffff0000, v135
	v_lshlrev_b32_e32 v88, 16, v137
	v_and_b32_e32 v89, 0xffff0000, v137
	v_pk_fma_f32 v[78:79], v[78:79], s[30:31], v[82:83] op_sel_hi:[1,0,1]
	v_pk_fma_f32 v[80:81], v[80:81], s[30:31], v[84:85] op_sel_hi:[1,0,1]
	v_pk_fma_f32 v[82:83], v[88:89], s[30:31], v[76:77] op_sel_hi:[1,0,1]
	v_pk_fma_f32 v[76:77], v[86:87], s[30:31], v[74:75] op_sel_hi:[1,0,1]
	v_cvt_pk_bf16_f32 v74, v78, v79
	v_add_co_u32_e32 v78, vcc, s46, v122
	v_cvt_pk_bf16_f32 v75, v80, v81
	v_cvt_pk_bf16_f32 v76, v76, v77
	v_cvt_pk_bf16_f32 v77, v82, v83
	v_addc_co_u32_e32 v79, vcc, 0, v123, vcc
	global_store_dwordx4 v[78:79], v[74:77], off
	v_lshlrev_b32_e32 v80, 16, v132
	v_and_b32_e32 v81, 0xffff0000, v132
	v_lshlrev_b32_e32 v74, 16, v130
	v_and_b32_e32 v75, 0xffff0000, v130
	v_lshlrev_b32_e32 v76, 16, v131
	v_and_b32_e32 v77, 0xffff0000, v131
	v_lshlrev_b32_e32 v82, 16, v133
	v_and_b32_e32 v83, 0xffff0000, v133
	v_pk_fma_f32 v[72:73], v[76:77], s[30:31], v[72:73] op_sel_hi:[1,0,1]
	v_pk_fma_f32 v[70:71], v[74:75], s[30:31], v[70:71] op_sel_hi:[1,0,1]
	v_pk_fma_f32 v[74:75], v[82:83], s[30:31], v[68:69] op_sel_hi:[1,0,1]
	v_pk_fma_f32 v[68:69], v[80:81], s[30:31], v[66:67] op_sel_hi:[1,0,1]
	v_cvt_pk_bf16_f32 v66, v70, v71
	v_cvt_pk_bf16_f32 v67, v72, v73
	v_cvt_pk_bf16_f32 v68, v68, v69
	v_cvt_pk_bf16_f32 v69, v74, v75
	global_store_dwordx4 v[78:79], v[66:69], off offset:256
	s_nop 1
	v_add_u32_e32 v66, 0x80, v173
	s_nop 0
	v_ashrrev_i32_e32 v67, 31, v66
	v_lshlrev_b64 v[66:67], 10, v[66:67]
	v_lshl_add_u64 v[66:67], v[66:67], 0, v[166:167]
	v_lshlrev_b64 v[98:99], 1, v[66:67]
	v_lshl_add_u64 v[90:91], s[12:13], 0, v[98:99]
	global_load_dwordx4 v[66:69], v[90:91], off
	global_load_dwordx4 v[70:73], v[90:91], off offset:256
	v_add_co_u32_e32 v78, vcc, s47, v90
	s_waitcnt vmcnt(0) lgkmcnt(0)
	v_lshlrev_b32_e32 v100, 16, v66
	v_addc_co_u32_e32 v79, vcc, 0, v91, vcc
	global_load_dwordx4 v[74:77], v[78:79], off
	s_nop 0
	global_load_dwordx4 v[78:81], v[78:79], off offset:256
	v_add_co_u32_e32 v86, vcc, s31, v90
	v_and_b32_e32 v101, 0xffff0000, v66
	s_nop 0
	v_addc_co_u32_e32 v87, vcc, 0, v91, vcc
	global_load_dwordx4 v[82:85], v[86:87], off
	s_nop 0
	global_load_dwordx4 v[86:89], v[86:87], off offset:256
	v_add_co_u32_e32 v94, vcc, s46, v90
	v_lshlrev_b32_e32 v66, 16, v67
	s_nop 0
	v_addc_co_u32_e32 v95, vcc, 0, v91, vcc
	global_load_dwordx4 v[90:93], v[94:95], off
	s_nop 0
	global_load_dwordx4 v[94:97], v[94:95], off offset:256
	v_and_b32_e32 v67, 0xffff0000, v67
	v_lshlrev_b32_e32 v102, 16, v68
	v_and_b32_e32 v103, 0xffff0000, v68
	v_lshlrev_b32_e32 v68, 16, v69
	v_and_b32_e32 v69, 0xffff0000, v69
	v_pk_fma_f32 v[64:65], v[66:67], s[30:31], v[64:65] op_sel_hi:[1,0,1]
	v_pk_fma_f32 v[62:63], v[100:101], s[30:31], v[62:63] op_sel_hi:[1,0,1]
	v_pk_fma_f32 v[66:67], v[68:69], s[30:31], v[60:61] op_sel_hi:[1,0,1]
	v_pk_fma_f32 v[60:61], v[102:103], s[30:31], v[58:59] op_sel_hi:[1,0,1]
	v_cvt_pk_bf16_f32 v58, v62, v63
	v_cvt_pk_bf16_f32 v59, v64, v65
	v_cvt_pk_bf16_f32 v60, v60, v61
	v_cvt_pk_bf16_f32 v61, v66, v67
	v_lshl_add_u64 v[62:63], s[24:25], 0, v[98:99]
	global_store_dwordx4 v[62:63], v[58:61], off
	v_lshlrev_b32_e32 v64, 16, v72
	v_and_b32_e32 v65, 0xffff0000, v72
	v_lshlrev_b32_e32 v58, 16, v70
	v_and_b32_e32 v59, 0xffff0000, v70
	v_lshlrev_b32_e32 v60, 16, v71
	v_and_b32_e32 v61, 0xffff0000, v71
	v_lshlrev_b32_e32 v66, 16, v73
	v_and_b32_e32 v67, 0xffff0000, v73
	v_pk_fma_f32 v[56:57], v[60:61], s[30:31], v[56:57] op_sel_hi:[1,0,1]
	v_pk_fma_f32 v[54:55], v[58:59], s[30:31], v[54:55] op_sel_hi:[1,0,1]
	v_pk_fma_f32 v[58:59], v[66:67], s[30:31], v[48:49] op_sel_hi:[1,0,1]
	v_pk_fma_f32 v[48:49], v[64:65], s[30:31], v[46:47] op_sel_hi:[1,0,1]
	v_cvt_pk_bf16_f32 v46, v54, v55
	v_cvt_pk_bf16_f32 v47, v56, v57
	v_cvt_pk_bf16_f32 v48, v48, v49
	v_cvt_pk_bf16_f32 v49, v58, v59
	global_store_dwordx4 v[62:63], v[46:49], off offset:256
	s_waitcnt vmcnt(0) lgkmcnt(0)
	v_lshlrev_b32_e32 v54, 16, v76
	v_lshlrev_b32_e32 v46, 16, v74
	v_and_b32_e32 v47, 0xffff0000, v74
	v_lshlrev_b32_e32 v48, 16, v75
	v_and_b32_e32 v49, 0xffff0000, v75
	v_and_b32_e32 v55, 0xffff0000, v76
	v_lshlrev_b32_e32 v56, 16, v77
	v_and_b32_e32 v57, 0xffff0000, v77
	v_pk_fma_f32 v[46:47], v[46:47], s[30:31], v[50:51] op_sel_hi:[1,0,1]
	v_pk_fma_f32 v[48:49], v[48:49], s[30:31], v[52:53] op_sel_hi:[1,0,1]
	v_pk_fma_f32 v[50:51], v[56:57], s[30:31], v[44:45] op_sel_hi:[1,0,1]
	v_pk_fma_f32 v[44:45], v[54:55], s[30:31], v[42:43] op_sel_hi:[1,0,1]
	v_cvt_pk_bf16_f32 v42, v46, v47
	v_add_co_u32_e32 v46, vcc, s47, v62
	v_cvt_pk_bf16_f32 v43, v48, v49
	v_cvt_pk_bf16_f32 v44, v44, v45
	v_cvt_pk_bf16_f32 v45, v50, v51
	v_addc_co_u32_e32 v47, vcc, 0, v63, vcc
	global_store_dwordx4 v[46:47], v[42:45], off
	v_lshlrev_b32_e32 v48, 16, v80
	v_and_b32_e32 v49, 0xffff0000, v80
	v_lshlrev_b32_e32 v42, 16, v78
	v_and_b32_e32 v43, 0xffff0000, v78
	v_lshlrev_b32_e32 v44, 16, v79
	v_and_b32_e32 v45, 0xffff0000, v79
	v_lshlrev_b32_e32 v50, 16, v81
	v_and_b32_e32 v51, 0xffff0000, v81
	v_pk_fma_f32 v[40:41], v[44:45], s[30:31], v[40:41] op_sel_hi:[1,0,1]
	v_pk_fma_f32 v[38:39], v[42:43], s[30:31], v[38:39] op_sel_hi:[1,0,1]
	v_pk_fma_f32 v[42:43], v[50:51], s[30:31], v[32:33] op_sel_hi:[1,0,1]
	v_pk_fma_f32 v[32:33], v[48:49], s[30:31], v[30:31] op_sel_hi:[1,0,1]
	v_cvt_pk_bf16_f32 v30, v38, v39
	v_cvt_pk_bf16_f32 v31, v40, v41
	v_cvt_pk_bf16_f32 v32, v32, v33
	v_cvt_pk_bf16_f32 v33, v42, v43
	global_store_dwordx4 v[46:47], v[30:33], off offset:256
	v_lshlrev_b32_e32 v38, 16, v84
	v_and_b32_e32 v39, 0xffff0000, v84
	v_lshlrev_b32_e32 v30, 16, v82
	v_and_b32_e32 v31, 0xffff0000, v82
	v_lshlrev_b32_e32 v32, 16, v83
	v_and_b32_e32 v33, 0xffff0000, v83
	v_lshlrev_b32_e32 v40, 16, v85
	v_and_b32_e32 v41, 0xffff0000, v85
	v_pk_fma_f32 v[30:31], v[30:31], s[30:31], v[34:35] op_sel_hi:[1,0,1]
	v_pk_fma_f32 v[32:33], v[32:33], s[30:31], v[36:37] op_sel_hi:[1,0,1]
	v_pk_fma_f32 v[34:35], v[40:41], s[30:31], v[28:29] op_sel_hi:[1,0,1]
	v_pk_fma_f32 v[28:29], v[38:39], s[30:31], v[26:27] op_sel_hi:[1,0,1]
	v_cvt_pk_bf16_f32 v26, v30, v31
	v_add_co_u32_e32 v30, vcc, s31, v62
	v_cvt_pk_bf16_f32 v27, v32, v33
	v_cvt_pk_bf16_f32 v28, v28, v29
	v_cvt_pk_bf16_f32 v29, v34, v35
	v_addc_co_u32_e32 v31, vcc, 0, v63, vcc
	global_store_dwordx4 v[30:31], v[26:29], off
	v_lshlrev_b32_e32 v32, 16, v88
	v_and_b32_e32 v33, 0xffff0000, v88
	v_lshlrev_b32_e32 v26, 16, v86
	v_and_b32_e32 v27, 0xffff0000, v86
	v_lshlrev_b32_e32 v28, 16, v87
	v_and_b32_e32 v29, 0xffff0000, v87
	v_lshlrev_b32_e32 v34, 16, v89
	v_and_b32_e32 v35, 0xffff0000, v89
	v_pk_fma_f32 v[24:25], v[28:29], s[30:31], v[24:25] op_sel_hi:[1,0,1]
	v_pk_fma_f32 v[22:23], v[26:27], s[30:31], v[22:23] op_sel_hi:[1,0,1]
	v_pk_fma_f32 v[26:27], v[34:35], s[30:31], v[16:17] op_sel_hi:[1,0,1]
	v_pk_fma_f32 v[16:17], v[32:33], s[30:31], v[14:15] op_sel_hi:[1,0,1]
	v_cvt_pk_bf16_f32 v14, v22, v23
	v_cvt_pk_bf16_f32 v15, v24, v25
	v_cvt_pk_bf16_f32 v16, v16, v17
	v_cvt_pk_bf16_f32 v17, v26, v27
	global_store_dwordx4 v[30:31], v[14:17], off offset:256
	v_lshlrev_b32_e32 v22, 16, v92
	v_and_b32_e32 v23, 0xffff0000, v92
	v_lshlrev_b32_e32 v14, 16, v90
	v_and_b32_e32 v15, 0xffff0000, v90
	v_lshlrev_b32_e32 v16, 16, v91
	v_and_b32_e32 v17, 0xffff0000, v91
	v_lshlrev_b32_e32 v24, 16, v93
	v_and_b32_e32 v25, 0xffff0000, v93
	v_pk_fma_f32 v[14:15], v[14:15], s[30:31], v[18:19] op_sel_hi:[1,0,1]
	v_pk_fma_f32 v[16:17], v[16:17], s[30:31], v[20:21] op_sel_hi:[1,0,1]
	v_pk_fma_f32 v[18:19], v[24:25], s[30:31], v[12:13] op_sel_hi:[1,0,1]
	v_pk_fma_f32 v[12:13], v[22:23], s[30:31], v[10:11] op_sel_hi:[1,0,1]
	v_cvt_pk_bf16_f32 v10, v14, v15
	v_add_co_u32_e32 v14, vcc, s46, v62
	v_cvt_pk_bf16_f32 v11, v16, v17
	v_cvt_pk_bf16_f32 v12, v12, v13
	v_cvt_pk_bf16_f32 v13, v18, v19
	v_addc_co_u32_e32 v15, vcc, 0, v63, vcc
	global_store_dwordx4 v[14:15], v[10:13], off
	v_lshlrev_b32_e32 v16, 16, v96
	v_and_b32_e32 v17, 0xffff0000, v96
	v_lshlrev_b32_e32 v10, 16, v94
	v_and_b32_e32 v11, 0xffff0000, v94
	v_lshlrev_b32_e32 v12, 16, v95
	v_and_b32_e32 v13, 0xffff0000, v95
	v_lshlrev_b32_e32 v18, 16, v97
	v_and_b32_e32 v19, 0xffff0000, v97
	v_pk_fma_f32 v[8:9], v[12:13], s[30:31], v[8:9] op_sel_hi:[1,0,1]
	v_pk_fma_f32 v[6:7], v[10:11], s[30:31], v[6:7] op_sel_hi:[1,0,1]
	v_pk_fma_f32 v[10:11], v[18:19], s[30:31], v[4:5] op_sel_hi:[1,0,1]
	v_pk_fma_f32 v[4:5], v[16:17], s[30:31], v[2:3] op_sel_hi:[1,0,1]
	v_cvt_pk_bf16_f32 v2, v6, v7
	v_cvt_pk_bf16_f32 v3, v8, v9
	v_cvt_pk_bf16_f32 v4, v4, v5
	v_cvt_pk_bf16_f32 v5, v10, v11
	s_and_b64 vcc, exec, s[34:35]
	global_store_dwordx4 v[14:15], v[2:5], off offset:256
	s_cbranch_vccz .LBB0_1046
	s_waitcnt vmcnt(0)
	s_cmpk_gt_u32 s4, 0xff
	s_cbranch_scc1 .LBB0_1051
	s_barrier

.LBB0_1068:
	s_or_b64 exec, exec, s[20:21]
	s_lshl_b32 s0, s7, 8
	s_add_i32 s0, s0, s97
	s_ashr_i32 s1, s0, 31
	s_lshl_b64 s[10:11], s[0:1], 11
	v_lshl_add_u64 v[38:39], v[54:55], 0, s[10:11]
	s_mov_b64 s[10:11], 0x4000
	v_add_co_u32_e32 v44, vcc, 0x4000, v38
	s_waitcnt lgkmcnt(0)
	s_barrier
	global_load_dwordx4 v[2:5], v[50:51], off
	global_load_dwordx4 v[6:9], v[50:51], off offset:1024
	global_load_dwordx4 v[10:13], v[52:53], off
	global_load_dwordx4 v[14:17], v[52:53], off offset:1024
	global_load_dwordx4 v[18:21], v[50:51], off offset:2048
	global_load_dwordx4 v[22:25], v[50:51], off offset:3072
	global_load_dwordx4 v[26:29], v[52:53], off offset:2048
	global_load_dwordx4 v[30:33], v[52:53], off offset:3072
	v_lshl_add_u64 v[42:43], v[38:39], 0, s[10:11]
	v_addc_co_u32_e32 v45, vcc, 0, v39, vcc
	global_load_dwordx2 v[36:37], v[38:39], off
	global_load_dwordx2 v[34:35], v[38:39], off offset:512
	global_load_dwordx2 v[40:41], v[38:39], off offset:1024
	s_nop 0
	global_load_dwordx2 v[38:39], v[38:39], off offset:1536
	s_nop 0
	global_load_dwordx2 v[60:61], v[44:45], off
	global_load_dwordx2 v[62:63], v[42:43], off offset:512
	global_load_dwordx2 v[64:65], v[42:43], off offset:1024
	global_load_dwordx2 v[66:67], v[42:43], off offset:1536
	s_mov_b32 s10, 0
	s_add_i32 s11, s0, 16
	s_mov_b32 s24, 0
	s_branch .LBB0_1071

.LBB0_1071:
	s_waitcnt vmcnt(0) lgkmcnt(0)
	v_lshlrev_b32_e32 v77, 16, v37
	v_lshlrev_b32_e32 v76, 16, v36
	v_and_b32_e32 v37, 0xffff0000, v37
	v_and_b32_e32 v36, 0xffff0000, v36
	v_pk_add_f32 v[68:69], v[76:77], v[36:37]
	v_lshlrev_b32_e32 v87, 16, v35
	v_lshlrev_b32_e32 v86, 16, v34
	v_and_b32_e32 v35, 0xffff0000, v35
	v_and_b32_e32 v34, 0xffff0000, v34
	v_lshlrev_b32_e32 v46, 16, v39
	v_and_b32_e32 v48, 0xffff0000, v39
	v_add_f32_e32 v39, v68, v69
	v_pk_add_f32 v[68:69], v[86:87], v[34:35]
	v_lshlrev_b32_e32 v42, 16, v40
	v_and_b32_e32 v43, 0xffff0000, v40
	v_lshlrev_b32_e32 v40, 16, v41
	v_and_b32_e32 v41, 0xffff0000, v41
	v_pk_add_f32 v[68:69], v[68:69], v[68:69] op_sel_hi:[0,1]
	v_lshlrev_b32_e32 v44, 16, v38
	v_and_b32_e32 v38, 0xffff0000, v38
	v_add_f32_e32 v49, 0, v39
	v_add_f32_e32 v45, v42, v43
	v_add_f32_e32 v39, v40, v41
	v_mov_b32_e32 v47, v69
	v_pk_add_f32 v[70:71], v[44:45], v[38:39]
	v_pk_add_f32 v[68:69], v[46:47], v[48:49]
	s_min_u32 s0, s24, 29
	v_pk_add_f32 v[68:69], v[70:71], v[68:69]
	s_lshl_b32 s0, s0, 3
	v_add_f32_e32 v39, v68, v69
	s_add_i32 s20, s11, s0
	s_nop 0
	v_add_f32_dpp v39, v39, v39 quad_perm:[1,0,3,2] row_mask:0xf bank_mask:0xf bound_ctrl:1
	s_nop 1
	v_add_f32_dpp v39, v39, v39 quad_perm:[2,3,0,1] row_mask:0xf bank_mask:0xf bound_ctrl:1
	s_nop 1
	v_add_f32_dpp v39, v39, v39 row_half_mirror row_mask:0xf bank_mask:0xf bound_ctrl:1
	s_nop 1
	v_add_f32_dpp v39, v39, v39 row_mirror row_mask:0xf bank_mask:0xf bound_ctrl:1
	s_nop 0
	v_readlane_b32 s21, v39, 16
	v_readlane_b32 s22, v39, 48
	v_readlane_b32 s0, v39, 0
	v_readlane_b32 s1, v39, 32
	v_mov_b32_e32 v68, s21
	v_mov_b32_e32 v69, s22
	v_pk_add_f32 v[68:69], s[0:1], v[68:69]
	s_nop 0
	v_add_f32_e32 v39, v68, v69
	v_fmac_f32_e32 v36, 0xba800000, v39
	v_fmac_f32_e32 v37, 0xba800000, v39
	v_fmac_f32_e32 v77, 0xba800000, v39
	v_fmac_f32_e32 v76, 0xba800000, v39
	v_mov_b32_e32 v88, v77
	v_mov_b32_e32 v89, v37
	v_mov_b32_e32 v77, v36
	v_fmac_f32_e32 v34, 0xba800000, v39
	v_fmac_f32_e32 v35, 0xba800000, v39
	v_fmac_f32_e32 v87, 0xba800000, v39
	v_pk_mul_f32 v[68:69], v[88:89], v[88:89]
	v_pk_mul_f32 v[36:37], v[76:77], v[76:77]
	v_fmac_f32_e32 v86, 0xba800000, v39
	v_mov_b32_e32 v90, v87
	v_mov_b32_e32 v91, v35
	v_mov_b32_e32 v87, v34
	v_pk_mov_b32 v[70:71], v[36:37], v[68:69] op_sel:[1,0]
	v_mov_b32_e32 v37, v69
	v_pk_mul_f32 v[68:69], v[90:91], v[90:91]
	v_pk_mul_f32 v[34:35], v[86:87], v[86:87]
	v_pk_add_f32 v[36:37], v[70:71], v[36:37]
	v_pk_mov_b32 v[70:71], v[34:35], v[68:69] op_sel:[1,0]
	v_mov_b32_e32 v35, v69
	v_pk_add_f32 v[34:35], v[70:71], v[34:35]
	v_fmac_f32_e32 v42, 0xba800000, v39
	v_pk_add_f32 v[34:35], v[34:35], v[34:35] op_sel_hi:[0,1]
	v_fmac_f32_e32 v43, 0xba800000, v39
	v_fmac_f32_e32 v40, 0xba800000, v39
	v_mul_f32_e32 v34, v42, v42
	v_fmac_f32_e32 v41, 0xba800000, v39
	v_pk_fma_f32 v[68:69], v[42:43], v[42:43], v[34:35] op_sel_hi:[1,1,0]
	v_mul_f32_e32 v34, v40, v40
	v_pk_add_f32 v[36:37], v[36:37], v[36:37] op_sel_hi:[0,1]
	v_pk_fma_f32 v[70:71], v[40:41], v[40:41], v[34:35] op_sel_hi:[1,1,0]
	v_fmac_f32_e32 v48, 0xba800000, v39
	v_fmac_f32_e32 v46, 0xba800000, v39
	v_fmac_f32_e32 v38, 0xba800000, v39
	v_fmac_f32_e32 v44, 0xba800000, v39
	v_mul_f32_e32 v68, v44, v44
	v_mul_f32_e32 v70, v38, v38
	v_mul_f32_e32 v36, v46, v46
	v_mul_f32_e32 v34, v48, v48
	v_pk_add_f32 v[68:69], v[68:69], v[70:71]
	v_pk_add_f32 v[34:35], v[36:37], v[34:35]
	v_mov_b32_e32 v47, v48
	v_pk_add_f32 v[34:35], v[68:69], v[34:35]
	s_nop 0
	v_add_f32_e32 v34, v34, v35
	s_nop 1
	v_add_f32_dpp v34, v34, v34 quad_perm:[1,0,3,2] row_mask:0xf bank_mask:0xf bound_ctrl:1
	s_nop 1
	v_add_f32_dpp v34, v34, v34 quad_perm:[2,3,0,1] row_mask:0xf bank_mask:0xf bound_ctrl:1
	s_nop 1
	v_add_f32_dpp v34, v34, v34 row_half_mirror row_mask:0xf bank_mask:0xf bound_ctrl:1
	s_nop 1
	v_add_f32_dpp v34, v34, v34 row_mirror row_mask:0xf bank_mask:0xf bound_ctrl:1
	s_nop 0
	v_readlane_b32 s21, v34, 16
	v_readlane_b32 s22, v34, 48
	v_readlane_b32 s0, v34, 0
	v_readlane_b32 s1, v34, 32
	v_mov_b32_e32 v34, s21
	v_mov_b32_e32 v35, s22
	v_pk_add_f32 v[34:35], s[0:1], v[34:35]
	s_mov_b32 s0, 0xf800000
	v_add_f32_e32 v34, v34, v35
	v_fmamk_f32 v34, v34, 0x3a800000, v82
	s_ashr_i32 s21, s20, 31
	v_mul_f32_e32 v35, 0x4f800000, v34
	v_cmp_gt_f32_e32 vcc, s0, v34
	s_lshl_b64 s[0:1], s[20:21], 11
	s_and_b32 s22, s24, 3
	v_cndmask_b32_e32 v36, v34, v35, vcc
	v_lshl_add_u64 v[34:35], v[54:55], 0, s[0:1]
	global_load_dwordx2 v[68:69], v[34:35], off
	global_load_dwordx2 v[70:71], v[34:35], off offset:512
	global_load_dwordx2 v[72:73], v[34:35], off offset:1024
	global_load_dwordx2 v[74:75], v[34:35], off offset:1536
	v_sqrt_f32_e32 v37, v36
	s_mul_i32 s23, s22, 0x810
	s_add_i32 s23, s87, s23
	v_add_u32_e32 v39, -1, v37
	v_fma_f32 v45, -v39, v37, v36
	v_cmp_ge_f32_e64 s[20:21], 0, v45
	v_add_u32_e32 v45, 1, v37
	s_nop 0
	v_cndmask_b32_e64 v39, v37, v39, s[20:21]
	v_fma_f32 v37, -v45, v37, v36
	v_cmp_lt_f32_e64 s[20:21], 0, v37
	s_nop 1
	v_cndmask_b32_e64 v37, v39, v45, s[20:21]
	v_mul_f32_e32 v39, 0x37800000, v37
	v_cndmask_b32_e32 v37, v37, v39, vcc
	v_cmp_class_f32_e32 vcc, v36, v83
	s_add_i32 s20, s4, s10
	s_ashr_i32 s21, s20, 31
	v_cndmask_b32_e32 v36, v37, v36, vcc
	v_div_scale_f32 v37, s[0:1], v36, v36, 1.0
	v_rcp_f32_e32 v39, v37
	s_lshl_b64 s[0:1], s[20:21], 11
	v_fma_f32 v34, -v37, v39, 1.0
	v_fmac_f32_e32 v39, v34, v39
	v_div_scale_f32 v34, vcc, 1.0, v36, 1.0
	v_mul_f32_e32 v35, v34, v39
	v_fma_f32 v45, -v37, v35, v34
	v_fmac_f32_e32 v35, v45, v39
	v_fma_f32 v34, -v37, v35, v34
	v_div_fmas_f32 v34, v34, v39, v35
	v_div_fixup_f32 v34, v34, v36, 1.0
	v_mov_b32_e32 v45, v38
	v_pk_mul_f32 v[36:37], v[76:77], v[34:35] op_sel_hi:[1,0]
	v_pk_mul_f32 v[76:77], v[88:89], v[34:35] op_sel_hi:[1,0]
	v_pk_mul_f32 v[38:39], v[44:45], v[34:35] op_sel_hi:[1,0]
	v_mov_b32_e32 v44, v168
	v_pk_fma_f32 v[76:77], v[4:5], v[76:77], v[12:13]
	v_pk_fma_f32 v[36:37], v[2:3], v[36:37], v[10:11]
	v_pk_mul_f32 v[86:87], v[86:87], v[34:35] op_sel_hi:[1,0]
	v_pk_mul_f32 v[88:89], v[90:91], v[34:35] op_sel_hi:[1,0]
	v_pk_fma_f32 v[86:87], v[6:7], v[86:87], v[14:15]
	v_pk_fma_f32 v[88:89], v[8:9], v[88:89], v[16:17]
	v_pk_mul_f32 v[42:43], v[42:43], v[34:35] op_sel_hi:[1,0]
	v_pk_mul_f32 v[40:41], v[40:41], v[34:35] op_sel_hi:[1,0]
	v_pk_mul_f32 v[34:35], v[46:47], v[34:35] op_sel_hi:[1,0]
	v_lshl_add_u32 v48, v44, 3, s23
	v_cvt_pk_bf16_f32 v44, v36, v37
	v_cvt_pk_bf16_f32 v45, v76, v77
	v_lshl_add_u64 v[46:47], v[56:57], 0, s[0:1]
	v_pk_fma_f32 v[40:41], v[20:21], v[40:41], v[28:29]
	v_pk_fma_f32 v[42:43], v[18:19], v[42:43], v[26:27]
	global_store_dwordx2 v[46:47], v[44:45], off
	ds_write_b64 v48, v[44:45] offset:33024
	v_cvt_pk_bf16_f32 v44, v86, v87
	v_cvt_pk_bf16_f32 v45, v88, v89
	v_pk_fma_f32 v[34:35], v[24:25], v[34:35], v[32:33]
	v_pk_fma_f32 v[38:39], v[22:23], v[38:39], v[30:31]
	global_store_dwordx2 v[46:47], v[44:45], off offset:512
	ds_write_b64 v48, v[44:45] offset:33536
	v_cvt_pk_bf16_f32 v44, v42, v43
	v_cvt_pk_bf16_f32 v45, v40, v41
	global_store_dwordx2 v[46:47], v[44:45], off offset:1024
	ds_write_b64 v48, v[44:45] offset:34048
	v_cvt_pk_bf16_f32 v44, v38, v39
	v_cvt_pk_bf16_f32 v45, v34, v35
	global_store_dwordx2 v[46:47], v[44:45], off offset:1536
	ds_write_b64 v48, v[44:45] offset:34560
	v_med3_f32 v36, v36, s6, v84
	v_med3_f32 v37, v37, s6, v84
	v_mov_b32_e32 v44, 0
	v_cvt_pk_fp8_f32 v44, v36, v37
	v_med3_f32 v36, v76, s6, v84
	v_med3_f32 v37, v77, s6, v84
	v_med3_f32 v45, v86, s6, v84
	v_cvt_pk_fp8_f32 v44, v36, v37 op_sel:[0,0,1]
	v_med3_f32 v46, v87, s6, v84
	v_mov_b32_e32 v47, 0
	v_cvt_pk_fp8_f32 v47, v45, v46
	s_lshl_b64 s[0:1], s[20:21], 10
	v_lshl_add_u64 v[36:37], v[58:59], 0, s[0:1]
	global_store_dword v[36:37], v44, off
	v_med3_f32 v44, v88, s6, v84
	v_med3_f32 v45, v89, s6, v84
	v_cvt_pk_fp8_f32 v47, v44, v45 op_sel:[0,0,1]
	v_med3_f32 v42, v42, s6, v84
	v_med3_f32 v43, v43, s6, v84
	v_mov_b32_e32 v44, 0
	v_cvt_pk_fp8_f32 v44, v42, v43
	v_med3_f32 v38, v38, s6, v84
	v_med3_f32 v39, v39, s6, v84
	v_mov_b32_e32 v42, 0
	v_cvt_pk_fp8_f32 v42, v38, v39
	v_med3_f32 v34, v34, s6, v84
	v_med3_f32 v35, v35, s6, v84
	v_med3_f32 v40, v40, s6, v84
	v_med3_f32 v41, v41, s6, v84
	v_cvt_pk_fp8_f32 v42, v34, v35 op_sel:[0,0,1]
	v_cvt_pk_fp8_f32 v44, v40, v41 op_sel:[0,0,1]
	s_cmp_lg_u32 s22, 3
	global_store_dword v[36:37], v47, off offset:256
	global_store_dword v[36:37], v44, off offset:512
	global_store_dword v[36:37], v42, off offset:768
	s_cbranch_scc1 .LBB0_1070
	v_mov_b32_e32 v76, v168
	s_nop 0
	v_and_b32_e32 v34, 3, v76
	v_mul_u32_u24_e32 v34, 0x810, v34
	v_and_b32_e32 v35, -16, v76
	v_add3_u32 v77, s87, v34, v35
	v_and_b32_e32 v34, 15, v76
	v_mul_u32_u24_e32 v34, 0x810, v34
	v_add3_u32 v85, 0, v34, v35
	ds_read_b128 v[34:37], v77 offset:33024
	ds_read_b128 v[38:41], v85
	s_waitcnt lgkmcnt(0)
	v_mfma_f32_16x16x32_bf16 v[34:37], v[34:37], v[38:41], 0
	ds_read_b128 v[38:41], v77 offset:33088
	ds_read_b128 v[42:45], v85 offset:64
	v_cmp_gt_i32_e32 vcc, 16, v76
	s_waitcnt lgkmcnt(0)
	v_mfma_f32_16x16x32_bf16 v[38:41], v[38:41], v[42:45], 0
	ds_read_b128 v[42:45], v77 offset:33152
	ds_read_b128 v[46:49], v85 offset:128
	s_waitcnt lgkmcnt(0)
	v_mfma_f32_16x16x32_bf16 v[42:45], v[42:45], v[46:49], 0
	ds_read_b128 v[46:49], v77 offset:33216
	ds_read_b128 v[86:89], v85 offset:192
	s_waitcnt lgkmcnt(0)
	v_mfma_f32_16x16x32_bf16 v[46:49], v[46:49], v[86:89], 0
	ds_read_b128 v[86:89], v77 offset:33280
	ds_read_b128 v[90:93], v85 offset:256
	s_waitcnt lgkmcnt(0)
	v_mfma_f32_16x16x32_bf16 v[34:37], v[86:89], v[90:93], v[34:37]
	ds_read_b128 v[86:89], v77 offset:33344
	ds_read_b128 v[90:93], v85 offset:320
	s_waitcnt lgkmcnt(0)
	v_mfma_f32_16x16x32_bf16 v[38:41], v[86:89], v[90:93], v[38:41]
	ds_read_b128 v[86:89], v77 offset:33408
	ds_read_b128 v[90:93], v85 offset:384
	s_waitcnt lgkmcnt(0)
	v_mfma_f32_16x16x32_bf16 v[42:45], v[86:89], v[90:93], v[42:45]
	ds_read_b128 v[86:89], v77 offset:33472
	ds_read_b128 v[90:93], v85 offset:448
	s_waitcnt lgkmcnt(0)
	v_mfma_f32_16x16x32_bf16 v[46:49], v[86:89], v[90:93], v[46:49]
	ds_read_b128 v[86:89], v77 offset:33536
	ds_read_b128 v[90:93], v85 offset:512
	s_waitcnt lgkmcnt(0)
	v_mfma_f32_16x16x32_bf16 v[34:37], v[86:89], v[90:93], v[34:37]
	ds_read_b128 v[86:89], v77 offset:33600
	ds_read_b128 v[90:93], v85 offset:576
	s_waitcnt lgkmcnt(0)
	v_mfma_f32_16x16x32_bf16 v[38:41], v[86:89], v[90:93], v[38:41]
	ds_read_b128 v[86:89], v77 offset:33664
	ds_read_b128 v[90:93], v85 offset:640
	s_waitcnt lgkmcnt(0)
	v_mfma_f32_16x16x32_bf16 v[42:45], v[86:89], v[90:93], v[42:45]
	ds_read_b128 v[86:89], v77 offset:33728
	ds_read_b128 v[90:93], v85 offset:704
	s_waitcnt lgkmcnt(0)
	v_mfma_f32_16x16x32_bf16 v[46:49], v[86:89], v[90:93], v[46:49]
	ds_read_b128 v[86:89], v77 offset:33792
	ds_read_b128 v[90:93], v85 offset:768
	s_waitcnt lgkmcnt(0)
	v_mfma_f32_16x16x32_bf16 v[34:37], v[86:89], v[90:93], v[34:37]
	ds_read_b128 v[86:89], v77 offset:33856
	ds_read_b128 v[90:93], v85 offset:832
	s_waitcnt lgkmcnt(0)
	v_mfma_f32_16x16x32_bf16 v[38:41], v[86:89], v[90:93], v[38:41]
	ds_read_b128 v[86:89], v77 offset:33920
	ds_read_b128 v[90:93], v85 offset:896
	s_waitcnt lgkmcnt(0)
	v_mfma_f32_16x16x32_bf16 v[42:45], v[86:89], v[90:93], v[42:45]
	ds_read_b128 v[86:89], v77 offset:33984
	ds_read_b128 v[90:93], v85 offset:960
	s_waitcnt lgkmcnt(0)
	v_mfma_f32_16x16x32_bf16 v[46:49], v[86:89], v[90:93], v[46:49]
	ds_read_b128 v[86:89], v77 offset:34048
	ds_read_b128 v[90:93], v85 offset:1024
	s_waitcnt lgkmcnt(0)
	v_mfma_f32_16x16x32_bf16 v[34:37], v[86:89], v[90:93], v[34:37]
	ds_read_b128 v[86:89], v77 offset:34112
	ds_read_b128 v[90:93], v85 offset:1088
	s_waitcnt lgkmcnt(0)
	v_mfma_f32_16x16x32_bf16 v[38:41], v[86:89], v[90:93], v[38:41]
	ds_read_b128 v[86:89], v77 offset:34176
	ds_read_b128 v[90:93], v85 offset:1152
	s_waitcnt lgkmcnt(0)
	v_mfma_f32_16x16x32_bf16 v[42:45], v[86:89], v[90:93], v[42:45]
	ds_read_b128 v[86:89], v77 offset:34240
	ds_read_b128 v[90:93], v85 offset:1216
	s_waitcnt lgkmcnt(0)
	v_mfma_f32_16x16x32_bf16 v[46:49], v[86:89], v[90:93], v[46:49]
	ds_read_b128 v[86:89], v77 offset:34304
	ds_read_b128 v[90:93], v85 offset:1280
	s_waitcnt lgkmcnt(0)
	v_mfma_f32_16x16x32_bf16 v[34:37], v[86:89], v[90:93], v[34:37]
	ds_read_b128 v[86:89], v77 offset:34368
	ds_read_b128 v[90:93], v85 offset:1344
	s_waitcnt lgkmcnt(0)
	v_mfma_f32_16x16x32_bf16 v[38:41], v[86:89], v[90:93], v[38:41]
	ds_read_b128 v[86:89], v77 offset:34432
	ds_read_b128 v[90:93], v85 offset:1408
	s_waitcnt lgkmcnt(0)
	v_mfma_f32_16x16x32_bf16 v[42:45], v[86:89], v[90:93], v[42:45]
	ds_read_b128 v[86:89], v77 offset:34496
	ds_read_b128 v[90:93], v85 offset:1472
	s_waitcnt lgkmcnt(0)
	v_mfma_f32_16x16x32_bf16 v[46:49], v[86:89], v[90:93], v[46:49]
	ds_read_b128 v[86:89], v77 offset:34560
	ds_read_b128 v[90:93], v85 offset:1536
	s_waitcnt lgkmcnt(0)
	v_mfma_f32_16x16x32_bf16 v[34:37], v[86:89], v[90:93], v[34:37]
	ds_read_b128 v[86:89], v77 offset:34624
	ds_read_b128 v[90:93], v85 offset:1600
	s_waitcnt lgkmcnt(0)
	v_mfma_f32_16x16x32_bf16 v[38:41], v[86:89], v[90:93], v[38:41]
	ds_read_b128 v[86:89], v77 offset:34688
	ds_read_b128 v[90:93], v85 offset:1664
	s_waitcnt lgkmcnt(0)
	v_mfma_f32_16x16x32_bf16 v[42:45], v[86:89], v[90:93], v[42:45]
	ds_read_b128 v[86:89], v77 offset:34752
	ds_read_b128 v[90:93], v85 offset:1728
	s_waitcnt lgkmcnt(0)
	v_mfma_f32_16x16x32_bf16 v[46:49], v[86:89], v[90:93], v[46:49]
	ds_read_b128 v[86:89], v77 offset:34816
	ds_read_b128 v[90:93], v85 offset:1792
	s_waitcnt lgkmcnt(0)
	v_mfma_f32_16x16x32_bf16 v[34:37], v[86:89], v[90:93], v[34:37]
	ds_read_b128 v[86:89], v77 offset:34880
	ds_read_b128 v[90:93], v85 offset:1856
	s_waitcnt lgkmcnt(0)
	v_mfma_f32_16x16x32_bf16 v[38:41], v[86:89], v[90:93], v[38:41]
	ds_read_b128 v[86:89], v77 offset:34944
	ds_read_b128 v[90:93], v85 offset:1920
	s_waitcnt lgkmcnt(0)
	v_mfma_f32_16x16x32_bf16 v[42:45], v[86:89], v[90:93], v[42:45]
	ds_read_b128 v[86:89], v77 offset:35008
	ds_read_b128 v[90:93], v85 offset:1984
	s_nop 1
	v_pk_add_f32 v[34:35], v[34:35], v[38:39]
	v_ashrrev_i32_e32 v77, 31, v76
	s_waitcnt lgkmcnt(0)
	v_mfma_f32_16x16x32_bf16 v[46:49], v[86:89], v[90:93], v[46:49]
	s_nop 7
	v_pk_add_f32 v[38:39], v[42:43], v[46:47]
	s_nop 0
	v_pk_add_f32 v[38:39], v[34:35], v[38:39]
	v_lshlrev_b64 v[34:35], 13, v[76:77]
	v_lshl_add_u64 v[34:35], s[30:31], 0, v[34:35]
	v_mov_b32_dpp v42, v38 quad_perm:[1,0,3,2] row_mask:0xf bank_mask:0xf bound_ctrl:1
	v_max_f32_e32 v42, v42, v42
	v_max_f32_e32 v42, v38, v42
	s_nop 1
	v_mov_b32_dpp v43, v42 quad_perm:[2,3,0,1] row_mask:0xf bank_mask:0xf bound_ctrl:1
	v_max_f32_e32 v43, v43, v43
	v_max_f32_e32 v42, v42, v43
	s_nop 1
	v_mov_b32_dpp v43, v42 row_half_mirror row_mask:0xf bank_mask:0xf bound_ctrl:1
	v_max_f32_e32 v43, v43, v43
	v_max_f32_e32 v42, v42, v43
	s_nop 1
	v_mov_b32_dpp v43, v42 row_mirror row_mask:0xf bank_mask:0xf bound_ctrl:1
	v_max_f32_e32 v43, v43, v43
	v_max_f32_e32 v42, v42, v43
	v_sub_f32_e32 v38, v38, v42
	v_mul_f32_e32 v38, 0x3fb8aa3b, v38
	v_exp_f32_e32 v38, v38
	s_nop 1
	v_add_f32_dpp v42, v38, v38 quad_perm:[1,0,3,2] row_mask:0xf bank_mask:0xf bound_ctrl:1
	s_nop 1
	v_add_f32_dpp v42, v42, v42 quad_perm:[2,3,0,1] row_mask:0xf bank_mask:0xf bound_ctrl:1
	s_nop 1
	v_add_f32_dpp v42, v42, v42 row_half_mirror row_mask:0xf bank_mask:0xf bound_ctrl:1
	s_nop 1
	v_mov_b32_dpp v43, v42 row_mirror row_mask:0xf bank_mask:0xf bound_ctrl:1
	s_and_saveexec_b64 s[22:23], vcc
	s_cbranch_execz .LBB0_1074
	v_add_f32_e32 v42, v42, v43
	v_rcp_f32_e32 v42, v42
	s_sub_i32 s21, s20, 24
	s_ashr_i32 s0, s21, 11
	s_ashr_i32 s1, s0, 31
	s_and_b32 s21, s21, 0x7ff
	s_lshl_b64 s[0:1], s[0:1], 17
	v_mul_f32_e32 v38, v38, v42
	v_lshl_add_u64 v[42:43], v[34:35], 0, s[0:1]
	s_lshl_b32 s28, s21, 2
	v_lshl_add_u64 v[42:43], v[42:43], 0, s[28:29]
	global_store_dword v[42:43], v38, off

.LBB0_1134:
	s_or_b64 exec, exec, s[34:35]
	v_cndmask_b32_e64 v2, -1, v3, s[52:53]
	v_cndmask_b32_e64 v12, -1, v5, s[58:59]
	v_cndmask_b32_e64 v3, -1, v6, s[60:61]
	v_cndmask_b32_e64 v6, -1, v7, s[54:55]
	v_cndmask_b32_e64 v4, -1, v8, s[48:49]
	v_cndmask_b32_e64 v7, -1, v9, s[44:45]
	v_cndmask_b32_e64 v5, -1, v10, s[40:41]
	v_cndmask_b32_e64 v8, -1, v11, s[30:31]
	s_add_i32 s5, s5, s90
	v_perm_b32 v5, v8, v5, s4
	v_perm_b32 v4, v7, v4, s4
	v_perm_b32 v3, v6, v3, s4
	v_perm_b32 v2, v12, v2, s4
	v_lshl_add_u64 v[6:7], v[18:19], 1, v[16:17]
	s_cmpk_lt_i32 s5, 0x200
	global_store_dwordx4 v[6:7], v[2:5], off
	s_waitcnt lgkmcnt(0)
	s_barrier
	s_cbranch_scc0 .LBB0_1182

.LBB0_1164:
	s_or_b64 exec, exec, s[64:65]
	v_sub_u32_e32 v2, v3, v2
	s_waitcnt lgkmcnt(0)
	v_add_u32_e32 v2, v2, v5
	v_add3_u32 v5, v2, v4, v6
	v_lshlrev_b32_e32 v4, 5, v22
	v_ashrrev_i32_e32 v3, 4, v22
	v_and_b32_e32 v4, 0x1e0, v4
	v_cmp_lt_i32_sdwa s[0:1], v5, v21 src0_sel:WORD_1 src1_sel:DWORD
	v_lshl_or_b32 v2, v3, 11, v28
	v_add_lshl_u32 v4, v4, v3, 8
	s_and_b64 s[0:1], s[58:59], s[0:1]
	v_min_i32_sdwa v3, v5, v21 dst_sel:DWORD dst_unused:UNUSED_PAD src0_sel:WORD_1 src1_sel:DWORD
	s_or_b64 s[52:53], s[52:53], s[0:1]
	v_add_u32_sdwa v3, v3, v5 dst_sel:DWORD dst_unused:UNUSED_PAD src0_sel:DWORD src1_sel:WORD_0
	s_and_saveexec_b64 s[64:65], s[52:53]
	s_cbranch_execz .LBB0_1166
	v_add_u32_e32 v6, v3, v4
	v_ashrrev_i32_e32 v7, 31, v6
	v_lshl_add_u64 v[6:7], v[6:7], 2, s[92:93]
	global_store_dword v[6:7], v2, off
.LBB0_1166:
	s_or_b64 exec, exec, s[64:65]
	v_cndmask_b32_e64 v7, 0, 1, s[58:59]
	v_add_u32_sdwa v7, v5, v7 dst_sel:DWORD dst_unused:UNUSED_PAD src0_sel:WORD_1 src1_sel:DWORD
	v_cmp_lt_i32_e64 s[58:59], v7, v21
	v_add_u32_sdwa v6, v5, v10 dst_sel:DWORD dst_unused:UNUSED_PAD src0_sel:WORD_0 src1_sel:DWORD
	s_and_b64 s[0:1], s[60:61], s[58:59]
	v_min_i32_e32 v5, v7, v21
	s_or_b64 s[58:59], s[62:63], s[0:1]
	v_add_u32_e32 v5, v5, v6
	s_and_saveexec_b64 s[64:65], s[58:59]
	s_cbranch_execz .LBB0_1168
	v_add_u32_e32 v8, v5, v4
	v_ashrrev_i32_e32 v9, 31, v8
	v_lshl_add_u64 v[8:9], v[8:9], 2, s[92:93]
	v_or_b32_e32 v10, 1, v2
	global_store_dword v[8:9], v10, off
.LBB0_1168:
	s_or_b64 exec, exec, s[64:65]
	v_cndmask_b32_e64 v8, 0, 1, s[62:63]
	v_add_u32_e32 v8, v6, v8
	v_cndmask_b32_e64 v6, 0, 1, s[60:61]
	v_add_u32_e32 v7, v7, v6
	v_cmp_lt_i32_e64 s[60:61], v7, v21
	s_and_b64 s[0:1], s[54:55], s[60:61]
	v_min_i32_e32 v6, v7, v21
	s_or_b64 s[60:61], s[56:57], s[0:1]
	v_add_u32_e32 v6, v6, v8
	s_and_saveexec_b64 s[62:63], s[60:61]
	s_cbranch_execz .LBB0_1170
	v_add_u32_e32 v10, v6, v4
	v_ashrrev_i32_e32 v11, 31, v10
	v_lshl_add_u64 v[10:11], v[10:11], 2, s[92:93]
	v_or_b32_e32 v9, 2, v2
	global_store_dword v[10:11], v9, off
.LBB0_1170:
	s_or_b64 exec, exec, s[62:63]
	v_cndmask_b32_e64 v9, 0, 1, s[56:57]
	v_add_u32_e32 v8, v8, v9
	v_cndmask_b32_e64 v9, 0, 1, s[54:55]
	v_add_u32_e32 v9, v7, v9
	v_cmp_lt_i32_e64 s[54:55], v9, v21
	s_and_b64 s[0:1], s[48:49], s[54:55]
	v_min_i32_e32 v7, v9, v21
	s_or_b64 s[54:55], s[50:51], s[0:1]
	v_add_u32_e32 v7, v7, v8
	s_and_saveexec_b64 s[56:57], s[54:55]
	s_cbranch_execz .LBB0_1172
	v_add_u32_e32 v10, v7, v4
	v_ashrrev_i32_e32 v11, 31, v10
	v_lshl_add_u64 v[10:11], v[10:11], 2, s[92:93]
	v_or_b32_e32 v12, 3, v2
	global_store_dword v[10:11], v12, off
.LBB0_1172:
	s_or_b64 exec, exec, s[56:57]
	v_cndmask_b32_e64 v10, 0, 1, s[50:51]
	v_add_u32_e32 v10, v8, v10
	v_cndmask_b32_e64 v8, 0, 1, s[48:49]
	v_add_u32_e32 v9, v9, v8
	v_cmp_lt_i32_e64 s[48:49], v9, v21
	s_and_b64 s[0:1], s[44:45], s[48:49]
	v_min_i32_e32 v8, v9, v21
	s_or_b64 s[48:49], s[46:47], s[0:1]
	v_add_u32_e32 v8, v8, v10
	s_and_saveexec_b64 s[50:51], s[48:49]
	s_cbranch_execz .LBB0_1174
	v_add_u32_e32 v22, v8, v4
	v_ashrrev_i32_e32 v23, 31, v22
	v_lshl_add_u64 v[22:23], v[22:23], 2, s[92:93]
	v_or_b32_e32 v11, 4, v2
	global_store_dword v[22:23], v11, off
.LBB0_1174:
	s_or_b64 exec, exec, s[50:51]
	v_cndmask_b32_e64 v11, 0, 1, s[46:47]
	v_add_u32_e32 v10, v10, v11
	v_cndmask_b32_e64 v11, 0, 1, s[44:45]
	v_add_u32_e32 v12, v9, v11
	v_cmp_lt_i32_e64 s[44:45], v12, v21
	s_and_b64 s[0:1], s[40:41], s[44:45]
	v_min_i32_e32 v9, v12, v21
	s_or_b64 s[44:45], s[42:43], s[0:1]
	v_add_u32_e32 v9, v9, v10
	s_and_saveexec_b64 s[46:47], s[44:45]
	s_cbranch_execz .LBB0_1176
	v_add_u32_e32 v22, v9, v4
	v_ashrrev_i32_e32 v23, 31, v22
	v_lshl_add_u64 v[22:23], v[22:23], 2, s[92:93]
	v_or_b32_e32 v11, 5, v2
	global_store_dword v[22:23], v11, off
.LBB0_1176:
	s_or_b64 exec, exec, s[46:47]
	v_cndmask_b32_e64 v11, 0, 1, s[42:43]
	v_add_u32_e32 v11, v10, v11
	v_cndmask_b32_e64 v10, 0, 1, s[40:41]
	v_add_u32_e32 v12, v12, v10
	v_cmp_lt_i32_e64 s[40:41], v12, v21
	s_and_b64 s[0:1], s[30:31], s[40:41]
	v_min_i32_e32 v10, v12, v21
	s_or_b64 s[40:41], s[36:37], s[0:1]
	v_add_u32_e32 v10, v10, v11
	s_and_saveexec_b64 s[42:43], s[40:41]
	s_cbranch_execz .LBB0_1178
	v_add_u32_e32 v22, v10, v4
	v_ashrrev_i32_e32 v23, 31, v22
	v_lshl_add_u64 v[22:23], v[22:23], 2, s[92:93]
	v_or_b32_e32 v20, 6, v2
	global_store_dword v[22:23], v20, off
.LBB0_1178:
	s_or_b64 exec, exec, s[42:43]
	v_cndmask_b32_e64 v22, 0, 1, s[30:31]
	v_add_u32_e32 v12, v12, v22
	v_cmp_lt_i32_e64 s[30:31], v12, v21
	v_cndmask_b32_e64 v20, 0, 1, s[36:37]
	s_and_b64 s[0:1], s[34:35], s[30:31]
	v_min_i32_e32 v12, v12, v21
	s_or_b64 s[30:31], s[38:39], s[0:1]
	v_add3_u32 v11, v11, v20, v12
	s_and_saveexec_b64 s[34:35], s[30:31]
	s_cbranch_execz .LBB0_1134
	v_add_u32_e32 v20, v11, v4
	v_ashrrev_i32_e32 v21, 31, v20
	v_lshl_add_u64 v[20:21], v[20:21], 2, s[92:93]
	v_or_b32_e32 v2, 7, v2
	global_store_dword v[20:21], v2, off
	s_branch .LBB0_1134

.LBB0_1239:
	s_sub_i32 s0, 0x200, s10
	s_min_i32 s41, s0, s90
	s_lshl_b32 s24, s41, 3
	s_ashr_i32 s25, s24, 31
	v_mov_b32_e32 v2, v0
	s_cmp_lt_i32 s2, s24
	s_cselect_b64 s[14:15], -1, 0
	s_cmp_ge_i32 s2, s24
	v_readfirstlane_b32 s42, v2
	s_cbranch_scc1 .LBB0_1287
	s_movk_i32 s0, 0xff
	v_cmp_lt_i32_e64 s[8:9], s0, v2
	s_movk_i32 s0, 0x100
	v_lshl_add_u32 v3, v2, 2, s95
	v_cmp_gt_i32_e64 s[12:13], s0, v2
	s_and_saveexec_b64 s[26:27], s[12:13]
	s_cbranch_execz .LBB0_1242
	s_or_b32 s0, s41, s80
	s_mul_i32 s0, s0, s76
	s_add_i32 s0, s0, s91
	s_ashr_i32 s1, s0, 31
	s_lshr_b32 s1, s1, 26
	s_add_i32 s1, s0, s1
	s_ashr_i32 s28, s1, 6
	s_lshl_b32 s28, s28, 3
	s_sub_i32 s29, s41, s28
	s_min_i32 s29, s29, 8
	s_abs_i32 s29, s29
	v_cvt_f32_u32_e32 v4, s29
	s_sub_i32 s30, 0, s29
	s_andn2_b32 s1, s1, 63
	s_sub_i32 s0, s0, s1
	v_rcp_iflag_f32_e32 v4, v4
	s_ashr_i32 s1, s0, 31
	s_abs_i32 s0, s0
	v_mul_f32_e32 v4, 0x4f7ffffe, v4
	v_cvt_u32_f32_e32 v4, v4
	s_nop 0
	v_readfirstlane_b32 s31, v4
	s_mul_i32 s30, s30, s31
	s_mul_hi_u32 s30, s31, s30
	s_add_i32 s31, s31, s30
	s_mul_hi_u32 s30, s0, s31
	s_mul_i32 s30, s30, s29
	s_sub_i32 s0, s0, s30
	s_sub_i32 s30, s0, s29
	s_cmp_ge_u32 s0, s29
	s_cselect_b32 s0, s30, s0
	s_sub_i32 s30, s0, s29
	s_cmp_ge_u32 s0, s29
	s_cselect_b32 s0, s30, s0
	s_xor_b32 s0, s0, s1
	s_sub_i32 s0, s0, s1
	s_add_i32 s1, s28, s10
	s_add_i32 s1, s1, s0
	v_lshl_add_u32 v4, s1, 8, v2
	v_ashrrev_i32_e32 v5, 31, v4
	v_lshl_add_u64 v[4:5], v[4:5], 2, s[18:19]
	global_load_dword v4, v[4:5], off
	s_waitcnt vmcnt(0) lgkmcnt(0)
	v_lshlrev_b32_e32 v4, 10, v4
	ds_write_b32 v3, v4
.LBB0_1242:
	s_or_b64 exec, exec, s[26:27]
	v_readlane_b32 s0, v254, 23
	v_mov_b64_e32 v[4:5], s[24:25]
	v_readlane_b32 s1, v254, 24
	s_nop 1
	v_cmp_ge_i64_e32 vcc, s[0:1], v[4:5]
	s_cbranch_vccnz .LBB0_1287
	s_and_saveexec_b64 s[26:27], s[12:13]
	s_cbranch_execz .LBB0_1245
	v_readlane_b32 s0, v254, 22
	s_or_b32 s0, s41, s0
	v_readlane_b32 s1, v254, 21
	s_mul_i32 s0, s0, s1
	s_add_i32 s0, s0, s89
	s_ashr_i32 s1, s0, 31
	s_lshr_b32 s1, s1, 26
	s_add_i32 s1, s0, s1
	s_ashr_i32 s28, s1, 6
	s_lshl_b32 s28, s28, 3
	s_sub_i32 s29, s41, s28
	s_min_i32 s29, s29, 8
	s_abs_i32 s29, s29
	v_cvt_f32_u32_e32 v4, s29
	s_sub_i32 s30, 0, s29
	s_andn2_b32 s1, s1, 63
	s_sub_i32 s0, s0, s1
	v_rcp_iflag_f32_e32 v4, v4
	s_ashr_i32 s1, s0, 31
	s_abs_i32 s0, s0
	v_mul_f32_e32 v4, 0x4f7ffffe, v4
	v_cvt_u32_f32_e32 v4, v4
	s_nop 0
	v_readfirstlane_b32 s31, v4
	s_mul_i32 s30, s30, s31
	s_mul_hi_u32 s30, s31, s30
	s_add_i32 s31, s31, s30
	s_mul_hi_u32 s30, s0, s31
	s_mul_i32 s30, s30, s29
	s_sub_i32 s0, s0, s30
	s_sub_i32 s30, s0, s29
	s_cmp_ge_u32 s0, s29
	s_cselect_b32 s0, s30, s0
	s_sub_i32 s30, s0, s29
	s_cmp_ge_u32 s0, s29
	s_cselect_b32 s0, s30, s0
	s_xor_b32 s0, s0, s1
	s_sub_i32 s0, s0, s1
	s_add_i32 s1, s28, s10
	s_add_i32 s1, s1, s0
	v_lshl_add_u32 v4, s1, 8, v2
	v_ashrrev_i32_e32 v5, 31, v4
	v_lshl_add_u64 v[4:5], v[4:5], 2, s[18:19]
	global_load_dword v4, v[4:5], off
	s_waitcnt vmcnt(0) lgkmcnt(0)
	v_lshlrev_b32_e32 v4, 10, v4
	ds_write_b32 v3, v4 offset:1024
.LBB0_1245:
	s_or_b64 exec, exec, s[26:27]
	v_readlane_b32 s0, v254, 28
	v_mov_b64_e32 v[4:5], s[24:25]
	v_readlane_b32 s1, v254, 29
	s_nop 1
	v_cmp_ge_i64_e32 vcc, s[0:1], v[4:5]
	s_cbranch_vccnz .LBB0_1287
	s_and_saveexec_b64 s[26:27], s[12:13]
	s_cbranch_execz .LBB0_1248
	v_readlane_b32 s0, v254, 27
	s_or_b32 s0, s41, s0
	v_readlane_b32 s1, v254, 26
	s_mul_i32 s0, s0, s1
	v_readlane_b32 s1, v254, 25
	s_add_i32 s0, s0, s1
	s_ashr_i32 s1, s0, 31
	s_lshr_b32 s1, s1, 26
	s_add_i32 s1, s0, s1
	s_ashr_i32 s28, s1, 6
	s_lshl_b32 s28, s28, 3
	s_sub_i32 s29, s41, s28
	s_min_i32 s29, s29, 8
	s_abs_i32 s29, s29
	v_cvt_f32_u32_e32 v4, s29
	s_sub_i32 s30, 0, s29
	s_andn2_b32 s1, s1, 63
	s_sub_i32 s0, s0, s1
	v_rcp_iflag_f32_e32 v4, v4
	s_ashr_i32 s1, s0, 31
	s_abs_i32 s0, s0
	v_mul_f32_e32 v4, 0x4f7ffffe, v4
	v_cvt_u32_f32_e32 v4, v4
	s_nop 0
	v_readfirstlane_b32 s31, v4
	s_mul_i32 s30, s30, s31
	s_mul_hi_u32 s30, s31, s30
	s_add_i32 s31, s31, s30
	s_mul_hi_u32 s30, s0, s31
	s_mul_i32 s30, s30, s29
	s_sub_i32 s0, s0, s30
	s_sub_i32 s30, s0, s29
	s_cmp_ge_u32 s0, s29
	s_cselect_b32 s0, s30, s0
	s_sub_i32 s30, s0, s29
	s_cmp_ge_u32 s0, s29
	s_cselect_b32 s0, s30, s0
	s_xor_b32 s0, s0, s1
	s_sub_i32 s0, s0, s1
	s_add_i32 s1, s28, s10
	s_add_i32 s1, s1, s0
	v_lshl_add_u32 v4, s1, 8, v2
	v_ashrrev_i32_e32 v5, 31, v4
	v_lshl_add_u64 v[4:5], v[4:5], 2, s[18:19]
	global_load_dword v4, v[4:5], off
	s_waitcnt vmcnt(0) lgkmcnt(0)
	v_lshlrev_b32_e32 v4, 10, v4
	ds_write_b32 v3, v4 offset:2048
.LBB0_1248:
	s_or_b64 exec, exec, s[26:27]
	v_readlane_b32 s0, v254, 33
	v_mov_b64_e32 v[4:5], s[24:25]
	v_readlane_b32 s1, v254, 34
	s_nop 1
	v_cmp_ge_i64_e32 vcc, s[0:1], v[4:5]
	s_cbranch_vccnz .LBB0_1287
	s_and_saveexec_b64 s[26:27], s[12:13]
	s_cbranch_execz .LBB0_1251
	v_readlane_b32 s0, v254, 32
	s_or_b32 s0, s41, s0
	v_readlane_b32 s1, v254, 31
	s_mul_i32 s0, s0, s1
	v_readlane_b32 s1, v254, 30
	s_add_i32 s0, s0, s1
	s_ashr_i32 s1, s0, 31
	s_lshr_b32 s1, s1, 26
	s_add_i32 s1, s0, s1
	s_ashr_i32 s28, s1, 6
	s_lshl_b32 s28, s28, 3
	s_sub_i32 s29, s41, s28
	s_min_i32 s29, s29, 8
	s_abs_i32 s29, s29
	v_cvt_f32_u32_e32 v4, s29
	s_sub_i32 s30, 0, s29
	s_andn2_b32 s1, s1, 63
	s_sub_i32 s0, s0, s1
	v_rcp_iflag_f32_e32 v4, v4
	s_ashr_i32 s1, s0, 31
	s_abs_i32 s0, s0
	v_mul_f32_e32 v4, 0x4f7ffffe, v4
	v_cvt_u32_f32_e32 v4, v4
	s_nop 0
	v_readfirstlane_b32 s31, v4
	s_mul_i32 s30, s30, s31
	s_mul_hi_u32 s30, s31, s30
	s_add_i32 s31, s31, s30
	s_mul_hi_u32 s30, s0, s31
	s_mul_i32 s30, s30, s29
	s_sub_i32 s0, s0, s30
	s_sub_i32 s30, s0, s29
	s_cmp_ge_u32 s0, s29
	s_cselect_b32 s0, s30, s0
	s_sub_i32 s30, s0, s29
	s_cmp_ge_u32 s0, s29
	s_cselect_b32 s0, s30, s0
	s_xor_b32 s0, s0, s1
	s_sub_i32 s0, s0, s1
	s_add_i32 s1, s28, s10
	s_add_i32 s1, s1, s0
	v_lshl_add_u32 v4, s1, 8, v2
	v_ashrrev_i32_e32 v5, 31, v4
	v_lshl_add_u64 v[4:5], v[4:5], 2, s[18:19]
	global_load_dword v4, v[4:5], off
	s_waitcnt vmcnt(0) lgkmcnt(0)
	v_lshlrev_b32_e32 v4, 10, v4
	ds_write_b32 v3, v4 offset:3072
.LBB0_1251:
	s_or_b64 exec, exec, s[26:27]
	v_readlane_b32 s0, v254, 38
	v_mov_b64_e32 v[4:5], s[24:25]
	v_readlane_b32 s1, v254, 39
	s_nop 1
	v_cmp_ge_i64_e32 vcc, s[0:1], v[4:5]
	s_cbranch_vccnz .LBB0_1287
	s_and_saveexec_b64 s[26:27], s[12:13]
	s_cbranch_execz .LBB0_1254
	v_readlane_b32 s0, v254, 37
	s_or_b32 s0, s41, s0
	v_readlane_b32 s1, v254, 36
	s_mul_i32 s0, s0, s1
	v_readlane_b32 s1, v254, 35
	s_add_i32 s0, s0, s1
	s_ashr_i32 s1, s0, 31
	s_lshr_b32 s1, s1, 26
	s_add_i32 s1, s0, s1
	s_ashr_i32 s28, s1, 6
	s_lshl_b32 s28, s28, 3
	s_sub_i32 s29, s41, s28
	s_min_i32 s29, s29, 8
	s_abs_i32 s29, s29
	v_cvt_f32_u32_e32 v4, s29
	s_sub_i32 s30, 0, s29
	s_andn2_b32 s1, s1, 63
	s_sub_i32 s0, s0, s1
	v_rcp_iflag_f32_e32 v4, v4
	s_ashr_i32 s1, s0, 31
	s_abs_i32 s0, s0
	v_mul_f32_e32 v4, 0x4f7ffffe, v4
	v_cvt_u32_f32_e32 v4, v4
	s_nop 0
	v_readfirstlane_b32 s31, v4
	s_mul_i32 s30, s30, s31
	s_mul_hi_u32 s30, s31, s30
	s_add_i32 s31, s31, s30
	s_mul_hi_u32 s30, s0, s31
	s_mul_i32 s30, s30, s29
	s_sub_i32 s0, s0, s30
	s_sub_i32 s30, s0, s29
	s_cmp_ge_u32 s0, s29
	s_cselect_b32 s0, s30, s0
	s_sub_i32 s30, s0, s29
	s_cmp_ge_u32 s0, s29
	s_cselect_b32 s0, s30, s0
	s_xor_b32 s0, s0, s1
	s_sub_i32 s0, s0, s1
	s_add_i32 s1, s28, s10
	s_add_i32 s1, s1, s0
	v_lshl_add_u32 v4, s1, 8, v2
	v_ashrrev_i32_e32 v5, 31, v4
	v_lshl_add_u64 v[4:5], v[4:5], 2, s[18:19]
	global_load_dword v4, v[4:5], off
	s_waitcnt vmcnt(0) lgkmcnt(0)
	v_lshlrev_b32_e32 v4, 10, v4
	ds_write_b32 v3, v4 offset:4096
.LBB0_1254:
	s_or_b64 exec, exec, s[26:27]
	v_readlane_b32 s0, v254, 43
	v_mov_b64_e32 v[4:5], s[24:25]
	v_readlane_b32 s1, v254, 44
	s_nop 1
	v_cmp_ge_i64_e32 vcc, s[0:1], v[4:5]
	s_cbranch_vccnz .LBB0_1287
	s_and_saveexec_b64 s[26:27], s[12:13]
	s_cbranch_execz .LBB0_1257
	v_readlane_b32 s0, v254, 42
	s_or_b32 s0, s41, s0
	v_readlane_b32 s1, v254, 41
	s_mul_i32 s0, s0, s1
	v_readlane_b32 s1, v254, 40
	s_add_i32 s0, s0, s1
	s_ashr_i32 s1, s0, 31
	s_lshr_b32 s1, s1, 26
	s_add_i32 s1, s0, s1
	s_ashr_i32 s28, s1, 6
	s_lshl_b32 s28, s28, 3
	s_sub_i32 s29, s41, s28
	s_min_i32 s29, s29, 8
	s_abs_i32 s29, s29
	v_cvt_f32_u32_e32 v4, s29
	s_sub_i32 s30, 0, s29
	s_andn2_b32 s1, s1, 63
	s_sub_i32 s0, s0, s1
	v_rcp_iflag_f32_e32 v4, v4
	s_ashr_i32 s1, s0, 31
	s_abs_i32 s0, s0
	v_mul_f32_e32 v4, 0x4f7ffffe, v4
	v_cvt_u32_f32_e32 v4, v4
	s_nop 0
	v_readfirstlane_b32 s31, v4
	s_mul_i32 s30, s30, s31
	s_mul_hi_u32 s30, s31, s30
	s_add_i32 s31, s31, s30
	s_mul_hi_u32 s30, s0, s31
	s_mul_i32 s30, s30, s29
	s_sub_i32 s0, s0, s30
	s_sub_i32 s30, s0, s29
	s_cmp_ge_u32 s0, s29
	s_cselect_b32 s0, s30, s0
	s_sub_i32 s30, s0, s29
	s_cmp_ge_u32 s0, s29
	s_cselect_b32 s0, s30, s0
	s_xor_b32 s0, s0, s1
	s_sub_i32 s0, s0, s1
	s_add_i32 s1, s28, s10
	s_add_i32 s1, s1, s0
	v_lshl_add_u32 v4, s1, 8, v2
	v_ashrrev_i32_e32 v5, 31, v4
	v_lshl_add_u64 v[4:5], v[4:5], 2, s[18:19]
	global_load_dword v4, v[4:5], off
	s_waitcnt vmcnt(0) lgkmcnt(0)
	v_lshlrev_b32_e32 v4, 10, v4
	ds_write_b32 v3, v4 offset:5120
.LBB0_1257:
	s_or_b64 exec, exec, s[26:27]
	v_readlane_b32 s0, v254, 48
	v_mov_b64_e32 v[4:5], s[24:25]
	v_readlane_b32 s1, v254, 49
	s_nop 1
	v_cmp_ge_i64_e32 vcc, s[0:1], v[4:5]
	s_cbranch_vccnz .LBB0_1287
	s_and_saveexec_b64 s[26:27], s[12:13]
	s_cbranch_execz .LBB0_1260
	v_readlane_b32 s0, v254, 47
	s_or_b32 s0, s41, s0
	v_readlane_b32 s1, v254, 46
	s_mul_i32 s0, s0, s1
	v_readlane_b32 s1, v254, 45
	s_add_i32 s0, s0, s1
	s_ashr_i32 s1, s0, 31
	s_lshr_b32 s1, s1, 26
	s_add_i32 s1, s0, s1
	s_ashr_i32 s28, s1, 6
	s_lshl_b32 s28, s28, 3
	s_sub_i32 s29, s41, s28
	s_min_i32 s29, s29, 8
	s_abs_i32 s29, s29
	v_cvt_f32_u32_e32 v4, s29
	s_sub_i32 s30, 0, s29
	s_andn2_b32 s1, s1, 63
	s_sub_i32 s0, s0, s1
	v_rcp_iflag_f32_e32 v4, v4
	s_ashr_i32 s1, s0, 31
	s_abs_i32 s0, s0
	v_mul_f32_e32 v4, 0x4f7ffffe, v4
	v_cvt_u32_f32_e32 v4, v4
	s_nop 0
	v_readfirstlane_b32 s31, v4
	s_mul_i32 s30, s30, s31
	s_mul_hi_u32 s30, s31, s30
	s_add_i32 s31, s31, s30
	s_mul_hi_u32 s30, s0, s31
	s_mul_i32 s30, s30, s29
	s_sub_i32 s0, s0, s30
	s_sub_i32 s30, s0, s29
	s_cmp_ge_u32 s0, s29
	s_cselect_b32 s0, s30, s0
	s_sub_i32 s30, s0, s29
	s_cmp_ge_u32 s0, s29
	s_cselect_b32 s0, s30, s0
	s_xor_b32 s0, s0, s1
	s_sub_i32 s0, s0, s1
	s_add_i32 s1, s28, s10
	s_add_i32 s1, s1, s0
	v_lshl_add_u32 v4, s1, 8, v2
	v_ashrrev_i32_e32 v5, 31, v4
	v_lshl_add_u64 v[4:5], v[4:5], 2, s[18:19]
	global_load_dword v4, v[4:5], off
	s_waitcnt vmcnt(0) lgkmcnt(0)
	v_lshlrev_b32_e32 v4, 10, v4
	ds_write_b32 v3, v4 offset:6144
.LBB0_1260:
	s_or_b64 exec, exec, s[26:27]
	v_readlane_b32 s0, v254, 53
	v_mov_b64_e32 v[4:5], s[24:25]
	v_readlane_b32 s1, v254, 54
	s_nop 1
	v_cmp_ge_i64_e32 vcc, s[0:1], v[4:5]
	s_cbranch_vccnz .LBB0_1287
	s_and_saveexec_b64 s[26:27], s[12:13]
	s_cbranch_execz .LBB0_1263
	v_readlane_b32 s0, v254, 52
	s_or_b32 s0, s41, s0
	v_readlane_b32 s1, v254, 51
	s_mul_i32 s0, s0, s1
	v_readlane_b32 s1, v254, 50
	s_add_i32 s0, s0, s1
	s_ashr_i32 s1, s0, 31
	s_lshr_b32 s1, s1, 26
	s_add_i32 s1, s0, s1
	s_ashr_i32 s28, s1, 6
	s_lshl_b32 s28, s28, 3
	s_sub_i32 s29, s41, s28
	s_min_i32 s29, s29, 8
	s_abs_i32 s29, s29
	v_cvt_f32_u32_e32 v4, s29
	s_sub_i32 s30, 0, s29
	s_andn2_b32 s1, s1, 63
	s_sub_i32 s0, s0, s1
	v_rcp_iflag_f32_e32 v4, v4
	s_ashr_i32 s1, s0, 31
	s_abs_i32 s0, s0
	v_mul_f32_e32 v4, 0x4f7ffffe, v4
	v_cvt_u32_f32_e32 v4, v4
	s_nop 0
	v_readfirstlane_b32 s31, v4
	s_mul_i32 s30, s30, s31
	s_mul_hi_u32 s30, s31, s30
	s_add_i32 s31, s31, s30
	s_mul_hi_u32 s30, s0, s31
	s_mul_i32 s30, s30, s29
	s_sub_i32 s0, s0, s30
	s_sub_i32 s30, s0, s29
	s_cmp_ge_u32 s0, s29
	s_cselect_b32 s0, s30, s0
	s_sub_i32 s30, s0, s29
	s_cmp_ge_u32 s0, s29
	s_cselect_b32 s0, s30, s0
	s_xor_b32 s0, s0, s1
	s_sub_i32 s0, s0, s1
	s_add_i32 s1, s28, s10
	s_add_i32 s1, s1, s0
	v_lshl_add_u32 v4, s1, 8, v2
	v_ashrrev_i32_e32 v5, 31, v4
	v_lshl_add_u64 v[4:5], v[4:5], 2, s[18:19]
	global_load_dword v4, v[4:5], off
	s_waitcnt vmcnt(0) lgkmcnt(0)
	v_lshlrev_b32_e32 v4, 10, v4
	ds_write_b32 v3, v4 offset:7168
.LBB0_1263:
	s_or_b64 exec, exec, s[26:27]
	v_readlane_b32 s0, v254, 58
	v_mov_b64_e32 v[4:5], s[24:25]
	v_readlane_b32 s1, v254, 59
	s_nop 1
	v_cmp_ge_i64_e32 vcc, s[0:1], v[4:5]
	s_cbranch_vccnz .LBB0_1287
	s_and_saveexec_b64 s[26:27], s[12:13]
	s_cbranch_execz .LBB0_1266
	v_readlane_b32 s0, v254, 57
	s_or_b32 s0, s41, s0
	v_readlane_b32 s1, v254, 56
	s_mul_i32 s0, s0, s1
	v_readlane_b32 s1, v254, 55
	s_add_i32 s0, s0, s1
	s_ashr_i32 s1, s0, 31
	s_lshr_b32 s1, s1, 26
	s_add_i32 s1, s0, s1
	s_ashr_i32 s28, s1, 6
	s_lshl_b32 s28, s28, 3
	s_sub_i32 s29, s41, s28
	s_min_i32 s29, s29, 8
	s_abs_i32 s29, s29
	v_cvt_f32_u32_e32 v4, s29
	s_sub_i32 s30, 0, s29
	s_andn2_b32 s1, s1, 63
	s_sub_i32 s0, s0, s1
	v_rcp_iflag_f32_e32 v4, v4
	s_ashr_i32 s1, s0, 31
	s_abs_i32 s0, s0
	v_mul_f32_e32 v4, 0x4f7ffffe, v4
	v_cvt_u32_f32_e32 v4, v4
	s_nop 0
	v_readfirstlane_b32 s31, v4
	s_mul_i32 s30, s30, s31
	s_mul_hi_u32 s30, s31, s30
	s_add_i32 s31, s31, s30
	s_mul_hi_u32 s30, s0, s31
	s_mul_i32 s30, s30, s29
	s_sub_i32 s0, s0, s30
	s_sub_i32 s30, s0, s29
	s_cmp_ge_u32 s0, s29
	s_cselect_b32 s0, s30, s0
	s_sub_i32 s30, s0, s29
	s_cmp_ge_u32 s0, s29
	s_cselect_b32 s0, s30, s0
	s_xor_b32 s0, s0, s1
	s_sub_i32 s0, s0, s1
	s_add_i32 s1, s28, s10
	s_add_i32 s1, s1, s0
	v_lshl_add_u32 v4, s1, 8, v2
	v_ashrrev_i32_e32 v5, 31, v4
	v_lshl_add_u64 v[4:5], v[4:5], 2, s[18:19]
	global_load_dword v4, v[4:5], off
	s_waitcnt vmcnt(0) lgkmcnt(0)
	v_lshlrev_b32_e32 v4, 10, v4
	ds_write_b32 v3, v4 offset:8192
.LBB0_1266:
	s_or_b64 exec, exec, s[26:27]
	v_readlane_b32 s0, v254, 63
	v_mov_b64_e32 v[4:5], s[24:25]
	v_readlane_b32 s1, v253, 0
	s_nop 1
	v_cmp_ge_i64_e32 vcc, s[0:1], v[4:5]
	s_cbranch_vccnz .LBB0_1287
	s_and_saveexec_b64 s[26:27], s[12:13]
	s_cbranch_execz .LBB0_1269
	v_readlane_b32 s0, v254, 62
	s_or_b32 s0, s41, s0
	v_readlane_b32 s1, v254, 61
	s_mul_i32 s0, s0, s1
	v_readlane_b32 s1, v254, 60
	s_add_i32 s0, s0, s1
	s_ashr_i32 s1, s0, 31
	s_lshr_b32 s1, s1, 26
	s_add_i32 s1, s0, s1
	s_ashr_i32 s28, s1, 6
	s_lshl_b32 s28, s28, 3
	s_sub_i32 s29, s41, s28
	s_min_i32 s29, s29, 8
	s_abs_i32 s29, s29
	v_cvt_f32_u32_e32 v4, s29
	s_sub_i32 s30, 0, s29
	s_andn2_b32 s1, s1, 63
	s_sub_i32 s0, s0, s1
	v_rcp_iflag_f32_e32 v4, v4
	s_ashr_i32 s1, s0, 31
	s_abs_i32 s0, s0
	v_mul_f32_e32 v4, 0x4f7ffffe, v4
	v_cvt_u32_f32_e32 v4, v4
	s_nop 0
	v_readfirstlane_b32 s31, v4
	s_mul_i32 s30, s30, s31
	s_mul_hi_u32 s30, s31, s30
	s_add_i32 s31, s31, s30
	s_mul_hi_u32 s30, s0, s31
	s_mul_i32 s30, s30, s29
	s_sub_i32 s0, s0, s30
	s_sub_i32 s30, s0, s29
	s_cmp_ge_u32 s0, s29
	s_cselect_b32 s0, s30, s0
	s_sub_i32 s30, s0, s29
	s_cmp_ge_u32 s0, s29
	s_cselect_b32 s0, s30, s0
	s_xor_b32 s0, s0, s1
	s_sub_i32 s0, s0, s1
	s_add_i32 s1, s28, s10
	s_add_i32 s1, s1, s0
	v_lshl_add_u32 v4, s1, 8, v2
	v_ashrrev_i32_e32 v5, 31, v4
	v_lshl_add_u64 v[4:5], v[4:5], 2, s[18:19]
	global_load_dword v4, v[4:5], off
	s_waitcnt vmcnt(0) lgkmcnt(0)
	v_lshlrev_b32_e32 v4, 10, v4
	ds_write_b32 v3, v4 offset:9216
.LBB0_1269:
	s_or_b64 exec, exec, s[26:27]
	v_readlane_b32 s0, v253, 4
	v_mov_b64_e32 v[4:5], s[24:25]
	v_readlane_b32 s1, v253, 5
	s_nop 1
	v_cmp_ge_i64_e32 vcc, s[0:1], v[4:5]
	s_cbranch_vccnz .LBB0_1287
	s_and_saveexec_b64 s[26:27], s[12:13]
	s_cbranch_execz .LBB0_1272
	v_readlane_b32 s0, v253, 3
	s_or_b32 s0, s41, s0
	v_readlane_b32 s1, v253, 2
	s_mul_i32 s0, s0, s1
	v_readlane_b32 s1, v253, 1
	s_add_i32 s0, s0, s1
	s_ashr_i32 s1, s0, 31
	s_lshr_b32 s1, s1, 26
	s_add_i32 s1, s0, s1
	s_ashr_i32 s28, s1, 6
	s_lshl_b32 s28, s28, 3
	s_sub_i32 s29, s41, s28
	s_min_i32 s29, s29, 8
	s_abs_i32 s29, s29
	v_cvt_f32_u32_e32 v4, s29
	s_sub_i32 s30, 0, s29
	s_andn2_b32 s1, s1, 63
	s_sub_i32 s0, s0, s1
	v_rcp_iflag_f32_e32 v4, v4
	s_ashr_i32 s1, s0, 31
	s_abs_i32 s0, s0
	v_mul_f32_e32 v4, 0x4f7ffffe, v4
	v_cvt_u32_f32_e32 v4, v4
	s_nop 0
	v_readfirstlane_b32 s31, v4
	s_mul_i32 s30, s30, s31
	s_mul_hi_u32 s30, s31, s30
	s_add_i32 s31, s31, s30
	s_mul_hi_u32 s30, s0, s31
	s_mul_i32 s30, s30, s29
	s_sub_i32 s0, s0, s30
	s_sub_i32 s30, s0, s29
	s_cmp_ge_u32 s0, s29
	s_cselect_b32 s0, s30, s0
	s_sub_i32 s30, s0, s29
	s_cmp_ge_u32 s0, s29
	s_cselect_b32 s0, s30, s0
	s_xor_b32 s0, s0, s1
	s_sub_i32 s0, s0, s1
	s_add_i32 s1, s28, s10
	s_add_i32 s1, s1, s0
	v_lshl_add_u32 v4, s1, 8, v2
	v_ashrrev_i32_e32 v5, 31, v4
	v_lshl_add_u64 v[4:5], v[4:5], 2, s[18:19]
	global_load_dword v4, v[4:5], off
	s_waitcnt vmcnt(0) lgkmcnt(0)
	v_lshlrev_b32_e32 v4, 10, v4
	ds_write_b32 v3, v4 offset:10240
.LBB0_1272:
	s_or_b64 exec, exec, s[26:27]
	v_readlane_b32 s0, v253, 9
	v_mov_b64_e32 v[4:5], s[24:25]
	v_readlane_b32 s1, v253, 10
	s_nop 1
	v_cmp_ge_i64_e32 vcc, s[0:1], v[4:5]
	s_cbranch_vccnz .LBB0_1287
	s_and_saveexec_b64 s[26:27], s[12:13]
	s_cbranch_execz .LBB0_1275
	v_readlane_b32 s0, v253, 8
	s_or_b32 s0, s41, s0
	v_readlane_b32 s1, v253, 7
	s_mul_i32 s0, s0, s1
	v_readlane_b32 s1, v253, 6
	s_add_i32 s0, s0, s1
	s_ashr_i32 s1, s0, 31
	s_lshr_b32 s1, s1, 26
	s_add_i32 s1, s0, s1
	s_ashr_i32 s28, s1, 6
	s_lshl_b32 s28, s28, 3
	s_sub_i32 s29, s41, s28
	s_min_i32 s29, s29, 8
	s_abs_i32 s29, s29
	v_cvt_f32_u32_e32 v4, s29
	s_sub_i32 s30, 0, s29
	s_andn2_b32 s1, s1, 63
	s_sub_i32 s0, s0, s1
	v_rcp_iflag_f32_e32 v4, v4
	s_ashr_i32 s1, s0, 31
	s_abs_i32 s0, s0
	v_mul_f32_e32 v4, 0x4f7ffffe, v4
	v_cvt_u32_f32_e32 v4, v4
	s_nop 0
	v_readfirstlane_b32 s31, v4
	s_mul_i32 s30, s30, s31
	s_mul_hi_u32 s30, s31, s30
	s_add_i32 s31, s31, s30
	s_mul_hi_u32 s30, s0, s31
	s_mul_i32 s30, s30, s29
	s_sub_i32 s0, s0, s30
	s_sub_i32 s30, s0, s29
	s_cmp_ge_u32 s0, s29
	s_cselect_b32 s0, s30, s0
	s_sub_i32 s30, s0, s29
	s_cmp_ge_u32 s0, s29
	s_cselect_b32 s0, s30, s0
	s_xor_b32 s0, s0, s1
	s_sub_i32 s0, s0, s1
	s_add_i32 s1, s28, s10
	s_add_i32 s1, s1, s0
	v_lshl_add_u32 v4, s1, 8, v2
	v_ashrrev_i32_e32 v5, 31, v4
	v_lshl_add_u64 v[4:5], v[4:5], 2, s[18:19]
	global_load_dword v4, v[4:5], off
	s_waitcnt vmcnt(0) lgkmcnt(0)
	v_lshlrev_b32_e32 v4, 10, v4
	ds_write_b32 v3, v4 offset:11264
.LBB0_1275:
	s_or_b64 exec, exec, s[26:27]
	v_readlane_b32 s0, v253, 14
	v_mov_b64_e32 v[4:5], s[24:25]
	v_readlane_b32 s1, v253, 15
	s_nop 1
	v_cmp_ge_i64_e32 vcc, s[0:1], v[4:5]
	s_cbranch_vccnz .LBB0_1287
	s_and_saveexec_b64 s[26:27], s[12:13]
	s_cbranch_execz .LBB0_1278
	v_readlane_b32 s0, v253, 13
	s_or_b32 s0, s41, s0
	v_readlane_b32 s1, v253, 12
	s_mul_i32 s0, s0, s1
	v_readlane_b32 s1, v253, 11
	s_add_i32 s0, s0, s1
	s_ashr_i32 s1, s0, 31
	s_lshr_b32 s1, s1, 26
	s_add_i32 s1, s0, s1
	s_ashr_i32 s28, s1, 6
	s_lshl_b32 s28, s28, 3
	s_sub_i32 s29, s41, s28
	s_min_i32 s29, s29, 8
	s_abs_i32 s29, s29
	v_cvt_f32_u32_e32 v4, s29
	s_sub_i32 s30, 0, s29
	s_andn2_b32 s1, s1, 63
	s_sub_i32 s0, s0, s1
	v_rcp_iflag_f32_e32 v4, v4
	s_ashr_i32 s1, s0, 31
	s_abs_i32 s0, s0
	v_mul_f32_e32 v4, 0x4f7ffffe, v4
	v_cvt_u32_f32_e32 v4, v4
	s_nop 0
	v_readfirstlane_b32 s31, v4
	s_mul_i32 s30, s30, s31
	s_mul_hi_u32 s30, s31, s30
	s_add_i32 s31, s31, s30
	s_mul_hi_u32 s30, s0, s31
	s_mul_i32 s30, s30, s29
	s_sub_i32 s0, s0, s30
	s_sub_i32 s30, s0, s29
	s_cmp_ge_u32 s0, s29
	s_cselect_b32 s0, s30, s0
	s_sub_i32 s30, s0, s29
	s_cmp_ge_u32 s0, s29
	s_cselect_b32 s0, s30, s0
	s_xor_b32 s0, s0, s1
	s_sub_i32 s0, s0, s1
	s_add_i32 s1, s28, s10
	s_add_i32 s1, s1, s0
	v_lshl_add_u32 v4, s1, 8, v2
	v_ashrrev_i32_e32 v5, 31, v4
	v_lshl_add_u64 v[4:5], v[4:5], 2, s[18:19]
	global_load_dword v4, v[4:5], off
	s_waitcnt vmcnt(0) lgkmcnt(0)
	v_lshlrev_b32_e32 v4, 10, v4
	ds_write_b32 v3, v4 offset:12288
.LBB0_1278:
	s_or_b64 exec, exec, s[26:27]
	v_readlane_b32 s0, v253, 19
	v_mov_b64_e32 v[4:5], s[24:25]
	v_readlane_b32 s1, v253, 20
	s_nop 1
	v_cmp_ge_i64_e32 vcc, s[0:1], v[4:5]
	s_cbranch_vccnz .LBB0_1287
	s_and_saveexec_b64 s[26:27], s[12:13]
	s_cbranch_execz .LBB0_1281
	v_readlane_b32 s0, v253, 18
	s_or_b32 s0, s41, s0
	v_readlane_b32 s1, v253, 17
	s_mul_i32 s0, s0, s1
	v_readlane_b32 s1, v253, 16
	s_add_i32 s0, s0, s1
	s_ashr_i32 s1, s0, 31
	s_lshr_b32 s1, s1, 26
	s_add_i32 s1, s0, s1
	s_ashr_i32 s28, s1, 6
	s_lshl_b32 s28, s28, 3
	s_sub_i32 s29, s41, s28
	s_min_i32 s29, s29, 8
	s_abs_i32 s29, s29
	v_cvt_f32_u32_e32 v4, s29
	s_sub_i32 s30, 0, s29
	s_andn2_b32 s1, s1, 63
	s_sub_i32 s0, s0, s1
	v_rcp_iflag_f32_e32 v4, v4
	s_ashr_i32 s1, s0, 31
	s_abs_i32 s0, s0
	v_mul_f32_e32 v4, 0x4f7ffffe, v4
	v_cvt_u32_f32_e32 v4, v4
	s_nop 0
	v_readfirstlane_b32 s31, v4
	s_mul_i32 s30, s30, s31
	s_mul_hi_u32 s30, s31, s30
	s_add_i32 s31, s31, s30
	s_mul_hi_u32 s30, s0, s31
	s_mul_i32 s30, s30, s29
	s_sub_i32 s0, s0, s30
	s_sub_i32 s30, s0, s29
	s_cmp_ge_u32 s0, s29
	s_cselect_b32 s0, s30, s0
	s_sub_i32 s30, s0, s29
	s_cmp_ge_u32 s0, s29
	s_cselect_b32 s0, s30, s0
	s_xor_b32 s0, s0, s1
	s_sub_i32 s0, s0, s1
	s_add_i32 s1, s28, s10
	s_add_i32 s1, s1, s0
	v_lshl_add_u32 v4, s1, 8, v2
	v_ashrrev_i32_e32 v5, 31, v4
	v_lshl_add_u64 v[4:5], v[4:5], 2, s[18:19]
	global_load_dword v4, v[4:5], off
	s_waitcnt vmcnt(0) lgkmcnt(0)
	v_lshlrev_b32_e32 v4, 10, v4
	ds_write_b32 v3, v4 offset:13312
.LBB0_1281:
	s_or_b64 exec, exec, s[26:27]
	v_readlane_b32 s0, v253, 24
	v_mov_b64_e32 v[4:5], s[24:25]
	v_readlane_b32 s1, v253, 25
	s_nop 1
	v_cmp_ge_i64_e32 vcc, s[0:1], v[4:5]
	s_cbranch_vccnz .LBB0_1287
	s_and_saveexec_b64 s[26:27], s[12:13]
	s_cbranch_execz .LBB0_1284
	v_readlane_b32 s0, v253, 23
	s_or_b32 s0, s41, s0
	v_readlane_b32 s1, v253, 22
	s_mul_i32 s0, s0, s1
	v_readlane_b32 s1, v253, 21
	s_add_i32 s0, s0, s1
	s_ashr_i32 s1, s0, 31
	s_lshr_b32 s1, s1, 26
	s_add_i32 s1, s0, s1
	s_ashr_i32 s12, s1, 6
	s_lshl_b32 s12, s12, 3
	s_sub_i32 s13, s41, s12
	s_min_i32 s13, s13, 8
	s_abs_i32 s13, s13
	v_cvt_f32_u32_e32 v4, s13
	s_sub_i32 s28, 0, s13
	s_andn2_b32 s1, s1, 63
	s_sub_i32 s0, s0, s1
	v_rcp_iflag_f32_e32 v4, v4
	s_ashr_i32 s1, s0, 31
	s_abs_i32 s0, s0
	v_mul_f32_e32 v4, 0x4f7ffffe, v4
	v_cvt_u32_f32_e32 v4, v4
	s_nop 0
	v_readfirstlane_b32 s29, v4
	s_mul_i32 s28, s28, s29
	s_mul_hi_u32 s28, s29, s28
	s_add_i32 s29, s29, s28
	s_mul_hi_u32 s28, s0, s29
	s_mul_i32 s28, s28, s13
	s_sub_i32 s0, s0, s28
	s_sub_i32 s28, s0, s13
	s_cmp_ge_u32 s0, s13
	s_cselect_b32 s0, s28, s0
	s_sub_i32 s28, s0, s13
	s_cmp_ge_u32 s0, s13
	s_cselect_b32 s0, s28, s0
	s_xor_b32 s0, s0, s1
	s_sub_i32 s0, s0, s1
	s_add_i32 s1, s12, s10
	s_add_i32 s1, s1, s0
	v_lshl_add_u32 v4, s1, 8, v2
	v_ashrrev_i32_e32 v5, 31, v4
	v_lshl_add_u64 v[4:5], v[4:5], 2, s[18:19]
	global_load_dword v4, v[4:5], off
	s_waitcnt vmcnt(0) lgkmcnt(0)
	v_lshlrev_b32_e32 v4, 10, v4
	ds_write_b32 v3, v4 offset:14336
.LBB0_1284:
	s_or_b64 exec, exec, s[26:27]
	v_readlane_b32 s0, v253, 27
	v_mov_b64_e32 v[4:5], s[24:25]
	v_readlane_b32 s1, v253, 28
	s_nop 1
	v_cmp_lt_i64_e32 vcc, s[0:1], v[4:5]
	s_xor_b64 s[0:1], s[8:9], -1
	s_and_b64 s[0:1], vcc, s[0:1]
	s_and_saveexec_b64 s[8:9], s[0:1]
	s_cbranch_execz .LBB0_1286
	v_readlane_b32 s0, v253, 30
	s_or_b32 s0, s41, s0
	v_readlane_b32 s1, v253, 29
	s_mul_i32 s0, s0, s1
	v_readlane_b32 s1, v253, 26
	s_add_i32 s0, s0, s1
	s_ashr_i32 s1, s0, 31
	s_lshr_b32 s1, s1, 26
	s_add_i32 s1, s0, s1
	s_ashr_i32 s12, s1, 6
	s_lshl_b32 s12, s12, 3
	s_sub_i32 s13, s41, s12
	s_min_i32 s13, s13, 8
	s_abs_i32 s13, s13
	v_cvt_f32_u32_e32 v4, s13
	s_sub_i32 s26, 0, s13
	s_andn2_b32 s1, s1, 63
	s_sub_i32 s0, s0, s1
	v_rcp_iflag_f32_e32 v4, v4
	s_ashr_i32 s1, s0, 31
	s_abs_i32 s0, s0
	v_mul_f32_e32 v4, 0x4f7ffffe, v4
	v_cvt_u32_f32_e32 v4, v4
	s_nop 0
	v_readfirstlane_b32 s27, v4
	s_mul_i32 s26, s26, s27
	s_mul_hi_u32 s26, s27, s26
	s_add_i32 s27, s27, s26
	s_mul_hi_u32 s26, s0, s27
	s_mul_i32 s26, s26, s13
	s_sub_i32 s0, s0, s26
	s_sub_i32 s26, s0, s13
	s_cmp_ge_u32 s0, s13
	s_cselect_b32 s0, s26, s0
	s_sub_i32 s26, s0, s13
	s_cmp_ge_u32 s0, s13
	s_cselect_b32 s0, s26, s0
	s_xor_b32 s0, s0, s1
	s_sub_i32 s0, s0, s1
	s_add_i32 s1, s12, s10
	s_add_i32 s1, s1, s0
	v_lshl_add_u32 v4, s1, 8, v2
	v_ashrrev_i32_e32 v5, 31, v4
	v_lshl_add_u64 v[4:5], v[4:5], 2, s[18:19]
	global_load_dword v4, v[4:5], off
	s_waitcnt vmcnt(0) lgkmcnt(0)
	v_lshlrev_b32_e32 v4, 10, v4
	ds_write_b32 v3, v4 offset:15360

.LBB0_1302:
	s_add_u32 s12, s36, 0x100
	s_addc_u32 s13, s37, 0
	s_add_u32 s34, s31, s36
	s_addc_u32 s35, s55, s37
	s_cmpk_eq_i32 s36, 0x300
	s_cselect_b64 vcc, -1, 0
	s_and_b64 s[0:1], vcc, exec
	s_cselect_b32 s1, 0, s12
	s_cselect_b32 s0, 0, s13
	s_cselect_b32 s34, s29, s34
	s_cselect_b32 s35, s27, s35
	s_add_u32 s38, s16, s1
	s_addc_u32 s39, s17, s0
	s_add_i32 s1, 0, 0x10000
	v_add_u32_e32 v14, s1, v197
	ds_read_b128 v[2:5], v14
	ds_read_b128 v[6:9], v14 offset:1024
	ds_read_b128 v[10:13], v14 offset:2048
	ds_read_b128 v[14:17], v14 offset:3072
	v_cndmask_b32_e32 v162, v168, v171, vcc
	v_cndmask_b32_e32 v184, v170, v198, vcc
	v_cndmask_b32_e32 v175, v172, v199, vcc
	v_cndmask_b32_e32 v173, v174, v200, vcc
	v_lshl_add_u64 v[18:19], v[178:179], 0, s[36:37]
	s_add_i32 m0, s45, 0xc000
	ds_read_b128 v[202:205], v169
	ds_read_b128 v[206:209], v169 offset:1024
	ds_read_b128 v[210:213], v169 offset:2048
	ds_read_b128 v[214:217], v169 offset:3072
	ds_read_b128 v[218:221], v169 offset:4096
	ds_read_b128 v[222:225], v169 offset:5120
	ds_read_b128 v[226:229], v169 offset:6144
	ds_read_b128 v[230:233], v169 offset:7168
	global_load_lds_dwordx4 v[18:19], off
	v_lshl_add_u64 v[18:19], v[176:177], 0, s[36:37]
	s_add_i32 m0, s45, 0xe000
	s_nop 0
	global_load_lds_dwordx4 v[18:19], off
	s_waitcnt lgkmcnt(8)
	s_waitcnt vmcnt(10)
	s_barrier
	s_waitcnt lgkmcnt(0)
	s_waitcnt lgkmcnt(0)
	v_mfma_scale_f32_16x16x128_f8f6f4 v[158:161], v[2:9], v[202:209], v[158:161], v188, v188 op_sel_hi:[0,0,0]
	v_mfma_scale_f32_16x16x128_f8f6f4 v[150:153], v[10:17], v[202:209], v[150:153], v188, v188 op_sel_hi:[0,0,0]
	v_mfma_scale_f32_16x16x128_f8f6f4 v[142:145], v[2:9], v[210:217], v[142:145], v188, v188 op_sel_hi:[0,0,0]
	v_mfma_scale_f32_16x16x128_f8f6f4 v[134:137], v[10:17], v[210:217], v[134:137], v188, v188 op_sel_hi:[0,0,0]
	v_mfma_scale_f32_16x16x128_f8f6f4 v[126:129], v[2:9], v[218:225], v[126:129], v188, v188 op_sel_hi:[0,0,0]
	v_mfma_scale_f32_16x16x128_f8f6f4 v[118:121], v[10:17], v[218:225], v[118:121], v188, v188 op_sel_hi:[0,0,0]
	v_mfma_scale_f32_16x16x128_f8f6f4 v[110:113], v[2:9], v[226:233], v[110:113], v188, v188 op_sel_hi:[0,0,0]
	v_mfma_scale_f32_16x16x128_f8f6f4 v[102:105], v[10:17], v[226:233], v[102:105], v188, v188 op_sel_hi:[0,0,0]
	s_barrier
	s_add_i32 s0, 0, 0x14000
	s_add_i32 s1, s1, s43
	v_add_u32_e32 v30, s0, v197
	v_lshl_add_u64 v[180:181], s[34:35], 0, v[164:165]
	s_mov_b32 m0, s1
	ds_read_b128 v[18:21], v30
	ds_read_b128 v[22:25], v30 offset:1024
	ds_read_b128 v[26:29], v30 offset:2048
	ds_read_b128 v[30:33], v30 offset:3072
	global_load_lds_dwordx4 v[180:181], off
	v_lshl_add_u64 v[182:183], s[34:35], 0, v[166:167]
	s_add_i32 m0, s1, 0x2000
	s_nop 0
	global_load_lds_dwordx4 v[182:183], off
	s_waitcnt vmcnt(10)
	s_barrier
	s_waitcnt lgkmcnt(0)
	s_waitcnt lgkmcnt(0)
	v_mfma_scale_f32_16x16x128_f8f6f4 v[154:157], v[18:25], v[202:209], v[154:157], v188, v188 op_sel_hi:[0,0,0]
	v_mfma_scale_f32_16x16x128_f8f6f4 v[146:149], v[26:33], v[202:209], v[146:149], v188, v188 op_sel_hi:[0,0,0]
	v_mfma_scale_f32_16x16x128_f8f6f4 v[138:141], v[18:25], v[210:217], v[138:141], v188, v188 op_sel_hi:[0,0,0]
	v_mfma_scale_f32_16x16x128_f8f6f4 v[130:133], v[26:33], v[210:217], v[130:133], v188, v188 op_sel_hi:[0,0,0]
	v_mfma_scale_f32_16x16x128_f8f6f4 v[122:125], v[18:25], v[218:225], v[122:125], v188, v188 op_sel_hi:[0,0,0]
	v_mfma_scale_f32_16x16x128_f8f6f4 v[114:117], v[26:33], v[218:225], v[114:117], v188, v188 op_sel_hi:[0,0,0]
	v_mfma_scale_f32_16x16x128_f8f6f4 v[106:109], v[18:25], v[226:233], v[106:109], v188, v188 op_sel_hi:[0,0,0]
	v_mfma_scale_f32_16x16x128_f8f6f4 v[98:101], v[26:33], v[226:233], v[98:101], v188, v188 op_sel_hi:[0,0,0]
	s_mov_b32 m0, s45
	s_barrier
	ds_read_b128 v[202:205], v169 offset:16384
	ds_read_b128 v[206:209], v169 offset:17408
	ds_read_b128 v[210:213], v169 offset:18432
	ds_read_b128 v[214:217], v169 offset:19456
	ds_read_b128 v[218:221], v169 offset:20480
	ds_read_b128 v[222:225], v169 offset:21504
	ds_read_b128 v[226:229], v169 offset:22528
	ds_read_b128 v[230:233], v169 offset:23552
	global_load_lds_dwordx4 v162, s[38:39]
	s_mov_b32 m0, s46
	v_mov_b32_e32 v185, v163
	global_load_lds_dwordx4 v184, s[38:39]
	s_waitcnt vmcnt(10)
	s_barrier
	s_waitcnt lgkmcnt(0)
	v_lshl_add_u64 v[186:187], s[38:39], 0, v[162:163]
	v_lshl_add_u64 v[184:185], s[38:39], 0, v[184:185]
	s_waitcnt lgkmcnt(0)
	v_mfma_scale_f32_16x16x128_f8f6f4 v[94:97], v[2:9], v[202:209], v[94:97], v188, v188 op_sel_hi:[0,0,0]
	v_mfma_scale_f32_16x16x128_f8f6f4 v[86:89], v[10:17], v[202:209], v[86:89], v188, v188 op_sel_hi:[0,0,0]
	v_mfma_scale_f32_16x16x128_f8f6f4 v[78:81], v[2:9], v[210:217], v[78:81], v188, v188 op_sel_hi:[0,0,0]
	v_mfma_scale_f32_16x16x128_f8f6f4 v[70:73], v[10:17], v[210:217], v[70:73], v188, v188 op_sel_hi:[0,0,0]
	v_mfma_scale_f32_16x16x128_f8f6f4 v[62:65], v[2:9], v[218:225], v[62:65], v188, v188 op_sel_hi:[0,0,0]
	v_mfma_scale_f32_16x16x128_f8f6f4 v[54:57], v[10:17], v[218:225], v[54:57], v188, v188 op_sel_hi:[0,0,0]
	v_mfma_scale_f32_16x16x128_f8f6f4 v[46:49], v[2:9], v[226:233], v[46:49], v188, v188 op_sel_hi:[0,0,0]
	v_mfma_scale_f32_16x16x128_f8f6f4 v[38:41], v[10:17], v[226:233], v[38:41], v188, v188 op_sel_hi:[0,0,0]
	s_barrier
	s_add_u32 s36, s34, 0x20000
	s_addc_u32 s37, s35, 0
	s_add_i32 s0, s0, s43
	v_lshl_add_u64 v[2:3], s[36:37], 0, v[164:165]
	s_mov_b32 m0, s0
	s_nop 0
	global_load_lds_dwordx4 v[2:3], off
	v_lshl_add_u64 v[2:3], s[36:37], 0, v[166:167]
	s_add_i32 m0, s0, 0x2000
	s_nop 0
	global_load_lds_dwordx4 v[2:3], off
	s_waitcnt vmcnt(10)
	s_barrier
	v_mfma_scale_f32_16x16x128_f8f6f4 v[90:93], v[18:25], v[202:209], v[90:93], v188, v188 op_sel_hi:[0,0,0]
	v_mfma_scale_f32_16x16x128_f8f6f4 v[82:85], v[26:33], v[202:209], v[82:85], v188, v188 op_sel_hi:[0,0,0]
	v_mfma_scale_f32_16x16x128_f8f6f4 v[74:77], v[18:25], v[210:217], v[74:77], v188, v188 op_sel_hi:[0,0,0]
	v_mfma_scale_f32_16x16x128_f8f6f4 v[66:69], v[26:33], v[210:217], v[66:69], v188, v188 op_sel_hi:[0,0,0]
	v_mfma_scale_f32_16x16x128_f8f6f4 v[58:61], v[18:25], v[218:225], v[58:61], v188, v188 op_sel_hi:[0,0,0]
	v_mfma_scale_f32_16x16x128_f8f6f4 v[50:53], v[26:33], v[218:225], v[50:53], v188, v188 op_sel_hi:[0,0,0]
	v_mfma_scale_f32_16x16x128_f8f6f4 v[42:45], v[18:25], v[226:233], v[42:45], v188, v188 op_sel_hi:[0,0,0]
	v_mfma_scale_f32_16x16x128_f8f6f4 v[34:37], v[26:33], v[226:233], v[34:37], v188, v188 op_sel_hi:[0,0,0]
	s_add_i32 s0, 0, 0x18000
	v_add_u32_e32 v14, s0, v197
	s_barrier
	ds_read_b128 v[2:5], v14
	ds_read_b128 v[6:9], v14 offset:1024
	ds_read_b128 v[10:13], v14 offset:2048
	ds_read_b128 v[14:17], v14 offset:3072
	s_mov_b32 m0, s47
	ds_read_b128 v[18:21], v169 offset:32768
	ds_read_b128 v[22:25], v169 offset:33792
	ds_read_b128 v[26:29], v169 offset:34816
	ds_read_b128 v[30:33], v169 offset:35840
	ds_read_b128 v[202:205], v169 offset:36864
	ds_read_b128 v[206:209], v169 offset:37888
	ds_read_b128 v[210:213], v169 offset:38912
	ds_read_b128 v[214:217], v169 offset:39936
	global_load_lds_dwordx4 v175, s[38:39]
	s_mov_b32 m0, s48
	s_nop 0
	global_load_lds_dwordx4 v173, s[38:39]
	s_waitcnt lgkmcnt(8)
	s_waitcnt vmcnt(10)
	s_barrier
	s_waitcnt lgkmcnt(0)
	s_waitcnt lgkmcnt(0)
	v_mfma_scale_f32_16x16x128_f8f6f4 v[158:161], v[2:9], v[18:25], v[158:161], v188, v188 op_sel_hi:[0,0,0]
	v_mfma_scale_f32_16x16x128_f8f6f4 v[150:153], v[10:17], v[18:25], v[150:153], v188, v188 op_sel_hi:[0,0,0]
	v_mfma_scale_f32_16x16x128_f8f6f4 v[142:145], v[2:9], v[26:33], v[142:145], v188, v188 op_sel_hi:[0,0,0]
	v_mfma_scale_f32_16x16x128_f8f6f4 v[134:137], v[10:17], v[26:33], v[134:137], v188, v188 op_sel_hi:[0,0,0]
	v_mfma_scale_f32_16x16x128_f8f6f4 v[126:129], v[2:9], v[202:209], v[126:129], v188, v188 op_sel_hi:[0,0,0]
	v_mfma_scale_f32_16x16x128_f8f6f4 v[118:121], v[10:17], v[202:209], v[118:121], v188, v188 op_sel_hi:[0,0,0]
	v_mfma_scale_f32_16x16x128_f8f6f4 v[110:113], v[2:9], v[210:217], v[110:113], v188, v188 op_sel_hi:[0,0,0]
	v_mfma_scale_f32_16x16x128_f8f6f4 v[102:105], v[10:17], v[210:217], v[102:105], v188, v188 op_sel_hi:[0,0,0]
	s_barrier
	s_add_i32 s36, 0, 0x1c000
	s_add_i32 s0, s0, s43
	v_add_u32_e32 v162, s36, v197
	v_lshl_add_u64 v[180:181], v[180:181], 0, s[22:23]
	s_mov_b32 m0, s0
	ds_read_b128 v[218:221], v162
	ds_read_b128 v[222:225], v162 offset:1024
	ds_read_b128 v[226:229], v162 offset:2048
	ds_read_b128 v[230:233], v162 offset:3072
	global_load_lds_dwordx4 v[180:181], off
	v_lshl_add_u64 v[180:181], v[182:183], 0, s[22:23]
	s_add_i32 m0, s0, 0x2000
	s_nop 0
	global_load_lds_dwordx4 v[180:181], off
	s_waitcnt vmcnt(10)
	s_barrier
	s_waitcnt lgkmcnt(0)
	s_waitcnt lgkmcnt(0)
	v_mfma_scale_f32_16x16x128_f8f6f4 v[154:157], v[218:225], v[18:25], v[154:157], v188, v188 op_sel_hi:[0,0,0]
	v_mfma_scale_f32_16x16x128_f8f6f4 v[146:149], v[226:233], v[18:25], v[146:149], v188, v188 op_sel_hi:[0,0,0]
	v_mfma_scale_f32_16x16x128_f8f6f4 v[138:141], v[218:225], v[26:33], v[138:141], v188, v188 op_sel_hi:[0,0,0]
	v_mfma_scale_f32_16x16x128_f8f6f4 v[130:133], v[226:233], v[26:33], v[130:133], v188, v188 op_sel_hi:[0,0,0]
	v_mfma_scale_f32_16x16x128_f8f6f4 v[122:125], v[218:225], v[202:209], v[122:125], v188, v188 op_sel_hi:[0,0,0]
	v_mfma_scale_f32_16x16x128_f8f6f4 v[114:117], v[226:233], v[202:209], v[114:117], v188, v188 op_sel_hi:[0,0,0]
	v_mfma_scale_f32_16x16x128_f8f6f4 v[106:109], v[218:225], v[210:217], v[106:109], v188, v188 op_sel_hi:[0,0,0]
	v_mfma_scale_f32_16x16x128_f8f6f4 v[98:101], v[226:233], v[210:217], v[98:101], v188, v188 op_sel_hi:[0,0,0]
	s_mov_b32 m0, s51
	v_lshl_add_u64 v[180:181], v[186:187], 0, s[22:23]
	s_barrier
	ds_read_b128 v[18:21], v169 offset:49152
	ds_read_b128 v[22:25], v169 offset:50176
	ds_read_b128 v[26:29], v169 offset:51200
	ds_read_b128 v[30:33], v169 offset:52224
	ds_read_b128 v[202:205], v169 offset:53248
	ds_read_b128 v[206:209], v169 offset:54272
	ds_read_b128 v[210:213], v169 offset:55296
	ds_read_b128 v[214:217], v169 offset:56320
	global_load_lds_dwordx4 v[180:181], off
	v_lshl_add_u64 v[180:181], v[184:185], 0, s[22:23]
	s_mov_b32 m0, s52
	s_nop 0
	global_load_lds_dwordx4 v[180:181], off
	s_waitcnt vmcnt(10)
	s_barrier
	s_waitcnt lgkmcnt(0)
	s_waitcnt lgkmcnt(0)
	v_mfma_scale_f32_16x16x128_f8f6f4 v[94:97], v[2:9], v[18:25], v[94:97], v188, v188 op_sel_hi:[0,0,0]
	v_mfma_scale_f32_16x16x128_f8f6f4 v[86:89], v[10:17], v[18:25], v[86:89], v188, v188 op_sel_hi:[0,0,0]
	v_mfma_scale_f32_16x16x128_f8f6f4 v[78:81], v[2:9], v[26:33], v[78:81], v188, v188 op_sel_hi:[0,0,0]
	v_mfma_scale_f32_16x16x128_f8f6f4 v[70:73], v[10:17], v[26:33], v[70:73], v188, v188 op_sel_hi:[0,0,0]
	v_mfma_scale_f32_16x16x128_f8f6f4 v[62:65], v[2:9], v[202:209], v[62:65], v188, v188 op_sel_hi:[0,0,0]
	v_mfma_scale_f32_16x16x128_f8f6f4 v[54:57], v[10:17], v[202:209], v[54:57], v188, v188 op_sel_hi:[0,0,0]
	v_mfma_scale_f32_16x16x128_f8f6f4 v[46:49], v[2:9], v[210:217], v[46:49], v188, v188 op_sel_hi:[0,0,0]
	v_mfma_scale_f32_16x16x128_f8f6f4 v[38:41], v[10:17], v[210:217], v[38:41], v188, v188 op_sel_hi:[0,0,0]
	s_barrier
	s_add_u32 s0, s34, 0x20080
	s_addc_u32 s1, s35, 0
	s_add_i32 s34, s36, s43
	v_lshl_add_u64 v[2:3], s[0:1], 0, v[164:165]
	s_mov_b32 m0, s34
	s_nop 0
	global_load_lds_dwordx4 v[2:3], off
	v_lshl_add_u64 v[2:3], s[0:1], 0, v[166:167]
	s_add_i32 m0, s34, 0x2000
	s_nop 0
	global_load_lds_dwordx4 v[2:3], off
	s_waitcnt vmcnt(10)
	s_barrier
	v_mfma_scale_f32_16x16x128_f8f6f4 v[90:93], v[218:225], v[18:25], v[90:93], v188, v188 op_sel_hi:[0,0,0]
	v_mfma_scale_f32_16x16x128_f8f6f4 v[82:85], v[226:233], v[18:25], v[82:85], v188, v188 op_sel_hi:[0,0,0]
	v_mfma_scale_f32_16x16x128_f8f6f4 v[74:77], v[218:225], v[26:33], v[74:77], v188, v188 op_sel_hi:[0,0,0]
	v_mfma_scale_f32_16x16x128_f8f6f4 v[66:69], v[226:233], v[26:33], v[66:69], v188, v188 op_sel_hi:[0,0,0]
	v_mfma_scale_f32_16x16x128_f8f6f4 v[58:61], v[218:225], v[202:209], v[58:61], v188, v188 op_sel_hi:[0,0,0]
	v_mfma_scale_f32_16x16x128_f8f6f4 v[50:53], v[226:233], v[202:209], v[50:53], v188, v188 op_sel_hi:[0,0,0]
	v_mfma_scale_f32_16x16x128_f8f6f4 v[42:45], v[218:225], v[210:217], v[42:45], v188, v188 op_sel_hi:[0,0,0]
	v_mfma_scale_f32_16x16x128_f8f6f4 v[34:37], v[226:233], v[210:217], v[34:37], v188, v188 op_sel_hi:[0,0,0]
	s_add_i32 s56, s56, 2
	s_cmp_gt_u32 s56, 5
	s_mov_b64 s[36:37], s[12:13]
	s_barrier
	s_cbranch_scc0 .LBB0_1302
	v_mul_f32_e32 v5, 0x3c800000, v158
	v_mul_f32_e32 v6, 0xbfb8aa3b, v5
	v_exp_f32_e32 v6, v6
	s_ashr_i32 s31, s30, 31
	s_ashr_i32 s29, s28, 31
	s_lshl_b64 s[12:13], s[30:31], 18
	v_add_f32_e32 v6, 1.0, v6
	v_rcp_f32_e32 v6, v6
	s_lshl_b64 s[28:29], s[28:29], 15
	v_mov_b32_e32 v3, v195
	s_add_u32 s0, s6, s12
	v_mul_f32_e32 v5, v5, v6
	v_mul_f32_e32 v6, 0x3c800000, v159
	v_mul_f32_e32 v7, 0xbfb8aa3b, v6
	v_exp_f32_e32 v7, v7
	v_mul_f32_e32 v5, v5, v154
	v_mul_f32_e32 v5, 0x3e000000, v5
	v_med3_f32 v5, v5, s40, v190
	v_add_f32_e32 v7, 1.0, v7
	v_rcp_f32_e32 v7, v7
	s_nop 15
	s_nop 15
	v_mov_b32_e32 v2, v196
	v_mul_f32_e32 v6, v6, v7
	v_mul_f32_e32 v7, 0x3c800000, v160
	v_mul_f32_e32 v8, 0xbfb8aa3b, v7
	v_exp_f32_e32 v8, v8
	v_mul_f32_e32 v6, v6, v155
	v_mul_f32_e32 v6, 0x3e000000, v6
	v_add_u32_e32 v4, s49, v3
	v_add_f32_e32 v8, 1.0, v8
	v_rcp_f32_e32 v8, v8
	s_addc_u32 s1, s7, s13
	s_add_u32 s12, s0, s28
	v_mul_f32_e32 v7, v7, v8
	v_mul_f32_e32 v8, 0x3c800000, v161
	v_mul_f32_e32 v9, 0xbfb8aa3b, v8
	v_exp_f32_e32 v9, v9
	v_mul_f32_e32 v7, v7, v156
	v_mul_f32_e32 v7, 0x3e000000, v7
	v_lshl_add_u32 v2, v2, 3, s50
	v_add_f32_e32 v9, 1.0, v9
	v_rcp_f32_e32 v9, v9
	s_addc_u32 s13, s1, s29
	v_ashrrev_i32_e32 v3, 31, v2
	s_and_b64 vcc, exec, s[8:9]
	v_mul_f32_e32 v8, v8, v9
	v_mul_f32_e32 v9, 0x3c800000, v150
	v_mul_f32_e32 v10, 0xbfb8aa3b, v9
	v_exp_f32_e32 v10, v10
	v_mul_f32_e32 v8, v8, v157
	v_mul_f32_e32 v8, 0x3e000000, v8
	v_mov_b32_e32 v174, v200
	v_add_f32_e32 v10, 1.0, v10
	v_rcp_f32_e32 v10, v10
	v_mov_b32_e32 v172, v199
	v_mov_b32_e32 v170, v198
	v_mov_b32_e32 v168, v171
	v_mul_f32_e32 v9, v9, v10
	v_mul_f32_e32 v10, 0x3c800000, v151
	v_mul_f32_e32 v11, 0xbfb8aa3b, v10
	v_exp_f32_e32 v11, v11
	v_mul_f32_e32 v9, v9, v146
	v_mul_f32_e32 v9, 0x3e000000, v9
	s_mov_b32 s28, s26
	v_add_f32_e32 v11, 1.0, v11
	v_rcp_f32_e32 v11, v11
	s_mov_b32 s30, s54
	s_mov_b64 s[34:35], s[14:15]
	v_mul_f32_e32 v10, v10, v11
	v_mul_f32_e32 v11, 0x3c800000, v152
	v_mul_f32_e32 v12, 0xbfb8aa3b, v11
	v_exp_f32_e32 v12, v12
	v_mul_f32_e32 v10, v10, v147
	v_mul_f32_e32 v10, 0x3e000000, v10
	v_add_f32_e32 v12, 1.0, v12
	v_rcp_f32_e32 v12, v12
	s_nop 0
	v_mul_f32_e32 v11, v11, v12
	v_mul_f32_e32 v12, 0x3c800000, v153
	v_mul_f32_e32 v13, 0xbfb8aa3b, v12
	v_exp_f32_e32 v13, v13
	v_mul_f32_e32 v11, v11, v148
	v_mul_f32_e32 v11, 0x3e000000, v11
	v_add_f32_e32 v13, 1.0, v13
	v_rcp_f32_e32 v13, v13
	s_nop 0
	v_mul_f32_e32 v12, v12, v13
	v_med3_f32 v13, v6, s40, v190
	v_mov_b32_e32 v6, v163
	v_cvt_pk_fp8_f32 v6, v5, v13
	v_med3_f32 v5, v7, s40, v190
	v_med3_f32 v7, v8, s40, v190
	v_med3_f32 v8, v10, s40, v190
	v_cvt_pk_fp8_f32 v6, v5, v7 op_sel:[0,0,1]
	v_med3_f32 v5, v9, s40, v190
	v_mov_b32_e32 v7, v163
	v_cvt_pk_fp8_f32 v7, v5, v8
	v_mul_f32_e32 v12, v12, v149
	v_mul_f32_e32 v12, 0x3e000000, v12
	v_med3_f32 v5, v11, s40, v190
	v_med3_f32 v8, v12, s40, v190
	v_cvt_pk_fp8_f32 v7, v5, v8 op_sel:[0,0,1]
	v_ashrrev_i32_e32 v5, 31, v4
	v_lshlrev_b64 v[8:9], 7, v[4:5]
	v_lshl_add_u64 v[8:9], s[12:13], 0, v[8:9]
	v_lshl_add_u64 v[8:9], v[8:9], 0, v[2:3]
	v_mul_f32_e32 v5, 0x3c800000, v142
	global_store_dwordx2 v[8:9], v[6:7], off
	v_mul_f32_e32 v6, 0xbfb8aa3b, v5
	v_exp_f32_e32 v6, v6
	s_nop 0
	v_add_f32_e32 v6, 1.0, v6
	v_rcp_f32_e32 v6, v6
	s_nop 0
	v_mul_f32_e32 v5, v5, v6
	v_mul_f32_e32 v6, 0x3c800000, v143
	v_mul_f32_e32 v7, 0xbfb8aa3b, v6
	v_exp_f32_e32 v7, v7
	v_mul_f32_e32 v5, v5, v138
	v_mul_f32_e32 v5, 0x3e000000, v5
	v_med3_f32 v5, v5, s40, v190
	v_add_f32_e32 v7, 1.0, v7
	v_rcp_f32_e32 v7, v7
	s_nop 0
	v_mul_f32_e32 v6, v6, v7
	v_mul_f32_e32 v6, v6, v139
	v_mul_f32_e32 v7, 0x3e000000, v6
	v_mul_f32_e32 v6, 0x3c800000, v144
	v_mul_f32_e32 v8, 0xbfb8aa3b, v6
	v_exp_f32_e32 v8, v8
	v_med3_f32 v7, v7, s40, v190
	v_add_f32_e32 v8, 1.0, v8
	v_rcp_f32_e32 v8, v8
	s_nop 0
	v_mul_f32_e32 v6, v6, v8
	v_mul_f32_e32 v6, v6, v140
	v_mul_f32_e32 v9, 0x3e000000, v6
	v_mul_f32_e32 v6, 0x3c800000, v145
	v_mul_f32_e32 v8, 0xbfb8aa3b, v6
	v_exp_f32_e32 v8, v8
	s_nop 0
	v_add_f32_e32 v8, 1.0, v8
	v_rcp_f32_e32 v8, v8
	s_nop 0
	v_mul_f32_e32 v6, v6, v8
	v_mul_f32_e32 v6, v6, v141
	v_mul_f32_e32 v10, 0x3e000000, v6
	v_mul_f32_e32 v6, 0x3c800000, v134
	v_mul_f32_e32 v8, 0xbfb8aa3b, v6
	v_exp_f32_e32 v8, v8
	s_nop 0
	v_add_f32_e32 v8, 1.0, v8
	v_rcp_f32_e32 v8, v8
	s_nop 0
	v_mul_f32_e32 v6, v6, v8
	v_mul_f32_e32 v6, v6, v130
	v_mul_f32_e32 v11, 0x3e000000, v6
	v_mul_f32_e32 v6, 0x3c800000, v135
	v_mul_f32_e32 v8, 0xbfb8aa3b, v6
	v_exp_f32_e32 v8, v8
	s_nop 0
	v_add_f32_e32 v8, 1.0, v8
	v_rcp_f32_e32 v8, v8
	s_nop 0
	v_mul_f32_e32 v6, v6, v8
	v_mul_f32_e32 v6, v6, v131
	v_mul_f32_e32 v12, 0x3e000000, v6
	v_mul_f32_e32 v6, 0x3c800000, v136
	v_mul_f32_e32 v8, 0xbfb8aa3b, v6
	v_exp_f32_e32 v8, v8
	s_nop 0
	v_add_f32_e32 v8, 1.0, v8
	v_rcp_f32_e32 v8, v8
	s_nop 0
	v_mul_f32_e32 v6, v6, v8
	v_mul_f32_e32 v6, v6, v132
	v_mul_f32_e32 v13, 0x3e000000, v6
	v_mul_f32_e32 v6, 0x3c800000, v137
	v_mul_f32_e32 v8, 0xbfb8aa3b, v6
	v_exp_f32_e32 v8, v8
	s_nop 0
	v_add_f32_e32 v8, 1.0, v8
	v_rcp_f32_e32 v8, v8
	s_nop 0
	v_mul_f32_e32 v6, v6, v8
	v_mov_b32_e32 v8, v163
	v_cvt_pk_fp8_f32 v8, v5, v7
	v_med3_f32 v5, v9, s40, v190
	v_med3_f32 v7, v10, s40, v190
	v_mov_b32_e32 v9, v163
	v_cvt_pk_fp8_f32 v8, v5, v7 op_sel:[0,0,1]
	v_med3_f32 v5, v11, s40, v190
	v_med3_f32 v7, v12, s40, v190
	v_cvt_pk_fp8_f32 v9, v5, v7
	v_mul_f32_e32 v6, v6, v133
	v_mul_f32_e32 v14, 0x3e000000, v6
	v_add_u32_e32 v6, 16, v4
	v_med3_f32 v5, v13, s40, v190
	v_med3_f32 v7, v14, s40, v190
	v_cvt_pk_fp8_f32 v9, v5, v7 op_sel:[0,0,1]
	v_ashrrev_i32_e32 v7, 31, v6
	v_lshlrev_b64 v[6:7], 7, v[6:7]
	v_lshl_add_u64 v[6:7], s[12:13], 0, v[6:7]
	v_lshl_add_u64 v[6:7], v[6:7], 0, v[2:3]
	v_mul_f32_e32 v5, 0x3c800000, v126
	global_store_dwordx2 v[6:7], v[8:9], off
	v_mul_f32_e32 v6, 0xbfb8aa3b, v5
	v_exp_f32_e32 v6, v6
	s_nop 0
	v_add_f32_e32 v6, 1.0, v6
	v_rcp_f32_e32 v6, v6
	s_nop 0
	v_mul_f32_e32 v5, v5, v6
	v_mul_f32_e32 v6, 0x3c800000, v127
	v_mul_f32_e32 v7, 0xbfb8aa3b, v6
	v_exp_f32_e32 v7, v7
	v_mul_f32_e32 v5, v5, v122
	v_mul_f32_e32 v5, 0x3e000000, v5
	v_med3_f32 v5, v5, s40, v190
	v_add_f32_e32 v7, 1.0, v7
	v_rcp_f32_e32 v7, v7
	s_nop 0
	v_mul_f32_e32 v6, v6, v7
	v_mul_f32_e32 v6, v6, v123
	v_mul_f32_e32 v7, 0x3e000000, v6
	v_mul_f32_e32 v6, 0x3c800000, v128
	v_mul_f32_e32 v8, 0xbfb8aa3b, v6
	v_exp_f32_e32 v8, v8
	v_med3_f32 v7, v7, s40, v190
	v_add_f32_e32 v8, 1.0, v8
	v_rcp_f32_e32 v8, v8
	s_nop 0
	v_mul_f32_e32 v6, v6, v8
	v_mul_f32_e32 v6, v6, v124
	v_mul_f32_e32 v9, 0x3e000000, v6
	v_mul_f32_e32 v6, 0x3c800000, v129
	v_mul_f32_e32 v8, 0xbfb8aa3b, v6
	v_exp_f32_e32 v8, v8
	s_nop 0
	v_add_f32_e32 v8, 1.0, v8
	v_rcp_f32_e32 v8, v8
	s_nop 0
	v_mul_f32_e32 v6, v6, v8
	v_mul_f32_e32 v6, v6, v125
	v_mul_f32_e32 v10, 0x3e000000, v6
	v_mul_f32_e32 v6, 0x3c800000, v118
	v_mul_f32_e32 v8, 0xbfb8aa3b, v6
	v_exp_f32_e32 v8, v8
	s_nop 0
	v_add_f32_e32 v8, 1.0, v8
	v_rcp_f32_e32 v8, v8
	s_nop 0
	v_mul_f32_e32 v6, v6, v8
	v_mul_f32_e32 v6, v6, v114
	v_mul_f32_e32 v11, 0x3e000000, v6
	v_mul_f32_e32 v6, 0x3c800000, v119
	v_mul_f32_e32 v8, 0xbfb8aa3b, v6
	v_exp_f32_e32 v8, v8
	s_nop 0
	v_add_f32_e32 v8, 1.0, v8
	v_rcp_f32_e32 v8, v8
	s_nop 0
	v_mul_f32_e32 v6, v6, v8
	v_mul_f32_e32 v6, v6, v115
	v_mul_f32_e32 v12, 0x3e000000, v6
	v_mul_f32_e32 v6, 0x3c800000, v120
	v_mul_f32_e32 v8, 0xbfb8aa3b, v6
	v_exp_f32_e32 v8, v8
	s_nop 0
	v_add_f32_e32 v8, 1.0, v8
	v_rcp_f32_e32 v8, v8
	s_nop 0
	v_mul_f32_e32 v6, v6, v8
	v_mul_f32_e32 v6, v6, v116
	v_mul_f32_e32 v13, 0x3e000000, v6
	v_mul_f32_e32 v6, 0x3c800000, v121
	v_mul_f32_e32 v8, 0xbfb8aa3b, v6
	v_exp_f32_e32 v8, v8
	s_nop 0
	v_add_f32_e32 v8, 1.0, v8
	v_rcp_f32_e32 v8, v8
	s_nop 0
	v_mul_f32_e32 v6, v6, v8
	v_mov_b32_e32 v8, v163
	v_cvt_pk_fp8_f32 v8, v5, v7
	v_med3_f32 v5, v9, s40, v190
	v_med3_f32 v7, v10, s40, v190
	v_mov_b32_e32 v9, v163
	v_cvt_pk_fp8_f32 v8, v5, v7 op_sel:[0,0,1]
	v_med3_f32 v5, v11, s40, v190
	v_med3_f32 v7, v12, s40, v190
	v_cvt_pk_fp8_f32 v9, v5, v7
	v_mul_f32_e32 v6, v6, v117
	v_mul_f32_e32 v14, 0x3e000000, v6
	v_add_u32_e32 v6, 32, v4
	v_med3_f32 v5, v13, s40, v190
	v_med3_f32 v7, v14, s40, v190
	v_cvt_pk_fp8_f32 v9, v5, v7 op_sel:[0,0,1]
	v_ashrrev_i32_e32 v7, 31, v6
	v_lshlrev_b64 v[6:7], 7, v[6:7]
	v_lshl_add_u64 v[6:7], s[12:13], 0, v[6:7]
	v_lshl_add_u64 v[6:7], v[6:7], 0, v[2:3]
	v_mul_f32_e32 v5, 0x3c800000, v110
	global_store_dwordx2 v[6:7], v[8:9], off
	v_mul_f32_e32 v6, 0xbfb8aa3b, v5
	v_exp_f32_e32 v6, v6
	s_nop 0
	v_add_f32_e32 v6, 1.0, v6
	v_rcp_f32_e32 v6, v6
	s_nop 0
	v_mul_f32_e32 v5, v5, v6
	v_mul_f32_e32 v6, 0x3c800000, v111
	v_mul_f32_e32 v7, 0xbfb8aa3b, v6
	v_exp_f32_e32 v7, v7
	v_mul_f32_e32 v5, v5, v106
	v_mul_f32_e32 v5, 0x3e000000, v5
	v_med3_f32 v5, v5, s40, v190
	v_add_f32_e32 v7, 1.0, v7
	v_rcp_f32_e32 v7, v7
	s_nop 0
	v_mul_f32_e32 v6, v6, v7
	v_mul_f32_e32 v6, v6, v107
	v_mul_f32_e32 v7, 0x3e000000, v6
	v_mul_f32_e32 v6, 0x3c800000, v112
	v_mul_f32_e32 v8, 0xbfb8aa3b, v6
	v_exp_f32_e32 v8, v8
	v_med3_f32 v7, v7, s40, v190
	v_add_f32_e32 v8, 1.0, v8
	v_rcp_f32_e32 v8, v8
	s_nop 0
	v_mul_f32_e32 v6, v6, v8
	v_mul_f32_e32 v6, v6, v108
	v_mul_f32_e32 v9, 0x3e000000, v6
	v_mul_f32_e32 v6, 0x3c800000, v113
	v_mul_f32_e32 v8, 0xbfb8aa3b, v6
	v_exp_f32_e32 v8, v8
	s_nop 0
	v_add_f32_e32 v8, 1.0, v8
	v_rcp_f32_e32 v8, v8
	s_nop 0
	v_mul_f32_e32 v6, v6, v8
	v_mul_f32_e32 v6, v6, v109
	v_mul_f32_e32 v10, 0x3e000000, v6
	v_mul_f32_e32 v6, 0x3c800000, v102
	v_mul_f32_e32 v8, 0xbfb8aa3b, v6
	v_exp_f32_e32 v8, v8
	s_nop 0
	v_add_f32_e32 v8, 1.0, v8
	v_rcp_f32_e32 v8, v8
	s_nop 0
	v_mul_f32_e32 v6, v6, v8
	v_mul_f32_e32 v6, v6, v98
	v_mul_f32_e32 v11, 0x3e000000, v6
	v_mul_f32_e32 v6, 0x3c800000, v103
	v_mul_f32_e32 v8, 0xbfb8aa3b, v6
	v_exp_f32_e32 v8, v8
	s_nop 0
	v_add_f32_e32 v8, 1.0, v8
	v_rcp_f32_e32 v8, v8
	s_nop 0
	v_mul_f32_e32 v6, v6, v8
	v_mul_f32_e32 v6, v6, v99
	v_mul_f32_e32 v12, 0x3e000000, v6
	v_mul_f32_e32 v6, 0x3c800000, v104
	v_mul_f32_e32 v8, 0xbfb8aa3b, v6
	v_exp_f32_e32 v8, v8
	s_nop 0
	v_add_f32_e32 v8, 1.0, v8
	v_rcp_f32_e32 v8, v8
	s_nop 0
	v_mul_f32_e32 v6, v6, v8
	v_mul_f32_e32 v6, v6, v100
	v_mul_f32_e32 v13, 0x3e000000, v6
	v_mul_f32_e32 v6, 0x3c800000, v105
	v_mul_f32_e32 v8, 0xbfb8aa3b, v6
	v_exp_f32_e32 v8, v8
	s_nop 0
	v_add_f32_e32 v8, 1.0, v8
	v_rcp_f32_e32 v8, v8
	s_nop 0
	v_mul_f32_e32 v6, v6, v8
	v_mov_b32_e32 v8, v163
	v_cvt_pk_fp8_f32 v8, v5, v7
	v_med3_f32 v5, v9, s40, v190
	v_med3_f32 v7, v10, s40, v190
	v_mov_b32_e32 v9, v163
	v_cvt_pk_fp8_f32 v8, v5, v7 op_sel:[0,0,1]
	v_med3_f32 v5, v11, s40, v190
	v_med3_f32 v7, v12, s40, v190
	v_cvt_pk_fp8_f32 v9, v5, v7
	v_mul_f32_e32 v6, v6, v101
	v_mul_f32_e32 v14, 0x3e000000, v6
	v_add_u32_e32 v6, 48, v4
	v_med3_f32 v5, v13, s40, v190
	v_med3_f32 v7, v14, s40, v190
	v_cvt_pk_fp8_f32 v9, v5, v7 op_sel:[0,0,1]
	v_ashrrev_i32_e32 v7, 31, v6
	v_lshlrev_b64 v[6:7], 7, v[6:7]
	v_lshl_add_u64 v[6:7], s[12:13], 0, v[6:7]
	v_lshl_add_u64 v[6:7], v[6:7], 0, v[2:3]
	v_mul_f32_e32 v5, 0x3c800000, v94
	global_store_dwordx2 v[6:7], v[8:9], off
	v_mul_f32_e32 v7, 0xbfb8aa3b, v5
	v_exp_f32_e32 v7, v7
	v_add_u32_e32 v6, 0x80, v4
	v_add_f32_e32 v7, 1.0, v7
	v_rcp_f32_e32 v7, v7
	s_nop 0
	v_mul_f32_e32 v5, v5, v7
	v_mul_f32_e32 v7, 0x3c800000, v95
	v_mul_f32_e32 v8, 0xbfb8aa3b, v7
	v_exp_f32_e32 v8, v8
	v_mul_f32_e32 v5, v5, v90
	v_mul_f32_e32 v5, 0x3e000000, v5
	v_med3_f32 v5, v5, s40, v190
	v_add_f32_e32 v8, 1.0, v8
	v_rcp_f32_e32 v8, v8
	s_nop 0
	v_mul_f32_e32 v7, v7, v8
	v_mul_f32_e32 v8, 0x3c800000, v96
	v_mul_f32_e32 v9, 0xbfb8aa3b, v8
	v_exp_f32_e32 v9, v9
	v_mul_f32_e32 v7, v7, v91
	v_mul_f32_e32 v7, 0x3e000000, v7
	v_med3_f32 v7, v7, s40, v190
	v_add_f32_e32 v9, 1.0, v9
	v_rcp_f32_e32 v9, v9
	s_nop 0
	v_mul_f32_e32 v8, v8, v9
	v_mul_f32_e32 v8, v8, v92
	v_mul_f32_e32 v9, 0x3e000000, v8
	v_mul_f32_e32 v8, 0x3c800000, v97
	v_mul_f32_e32 v10, 0xbfb8aa3b, v8
	v_exp_f32_e32 v10, v10
	s_nop 0
	v_add_f32_e32 v10, 1.0, v10
	v_rcp_f32_e32 v10, v10
	s_nop 0
	v_mul_f32_e32 v8, v8, v10
	v_mul_f32_e32 v8, v8, v93
	v_mul_f32_e32 v10, 0x3e000000, v8
	v_mul_f32_e32 v8, 0x3c800000, v86
	v_mul_f32_e32 v11, 0xbfb8aa3b, v8
	v_exp_f32_e32 v11, v11
	s_nop 0
	v_add_f32_e32 v11, 1.0, v11
	v_rcp_f32_e32 v11, v11
	s_nop 0
	v_mul_f32_e32 v8, v8, v11
	v_mul_f32_e32 v8, v8, v82
	v_mul_f32_e32 v11, 0x3e000000, v8
	v_mul_f32_e32 v8, 0x3c800000, v87
	v_mul_f32_e32 v12, 0xbfb8aa3b, v8
	v_exp_f32_e32 v12, v12
	s_nop 0
	v_add_f32_e32 v12, 1.0, v12
	v_rcp_f32_e32 v12, v12
	s_nop 0
	v_mul_f32_e32 v8, v8, v12
	v_mul_f32_e32 v8, v8, v83
	v_mul_f32_e32 v12, 0x3e000000, v8
	v_mul_f32_e32 v8, 0x3c800000, v88
	v_mul_f32_e32 v13, 0xbfb8aa3b, v8
	v_exp_f32_e32 v13, v13
	s_nop 0
	v_add_f32_e32 v13, 1.0, v13
	v_rcp_f32_e32 v13, v13
	s_nop 0
	v_mul_f32_e32 v8, v8, v13
	v_mul_f32_e32 v8, v8, v84
	v_mul_f32_e32 v13, 0x3e000000, v8
	v_mul_f32_e32 v8, 0x3c800000, v89
	v_mul_f32_e32 v14, 0xbfb8aa3b, v8
	v_exp_f32_e32 v14, v14
	s_nop 0
	v_add_f32_e32 v14, 1.0, v14
	v_rcp_f32_e32 v14, v14
	s_nop 0
	v_mul_f32_e32 v8, v8, v14
	v_mul_f32_e32 v8, v8, v85
	v_mul_f32_e32 v14, 0x3e000000, v8
	v_mov_b32_e32 v8, v163
	v_cvt_pk_fp8_f32 v8, v5, v7
	v_med3_f32 v5, v9, s40, v190
	v_med3_f32 v7, v10, s40, v190
	v_mov_b32_e32 v9, v163
	v_cvt_pk_fp8_f32 v8, v5, v7 op_sel:[0,0,1]
	v_med3_f32 v5, v11, s40, v190
	v_med3_f32 v7, v12, s40, v190
	v_cvt_pk_fp8_f32 v9, v5, v7
	v_med3_f32 v5, v13, s40, v190
	v_med3_f32 v7, v14, s40, v190
	v_cvt_pk_fp8_f32 v9, v5, v7 op_sel:[0,0,1]
	v_ashrrev_i32_e32 v7, 31, v6
	v_lshlrev_b64 v[6:7], 7, v[6:7]
	v_lshl_add_u64 v[6:7], s[12:13], 0, v[6:7]
	v_lshl_add_u64 v[6:7], v[6:7], 0, v[2:3]
	v_mul_f32_e32 v5, 0x3c800000, v78
	global_store_dwordx2 v[6:7], v[8:9], off
	v_mul_f32_e32 v6, 0xbfb8aa3b, v5
	v_exp_f32_e32 v6, v6
	s_nop 0
	v_add_f32_e32 v6, 1.0, v6
	v_rcp_f32_e32 v6, v6
	s_nop 0
	v_mul_f32_e32 v5, v5, v6
	v_mul_f32_e32 v6, 0x3c800000, v79
	v_mul_f32_e32 v7, 0xbfb8aa3b, v6
	v_exp_f32_e32 v7, v7
	v_mul_f32_e32 v5, v5, v74
	v_mul_f32_e32 v5, 0x3e000000, v5
	v_med3_f32 v5, v5, s40, v190
	v_add_f32_e32 v7, 1.0, v7
	v_rcp_f32_e32 v7, v7
	s_nop 0
	v_mul_f32_e32 v6, v6, v7
	v_mul_f32_e32 v6, v6, v75
	v_mul_f32_e32 v7, 0x3e000000, v6
	v_mul_f32_e32 v6, 0x3c800000, v80
	v_mul_f32_e32 v8, 0xbfb8aa3b, v6
	v_exp_f32_e32 v8, v8
	v_med3_f32 v7, v7, s40, v190
	v_add_f32_e32 v8, 1.0, v8
	v_rcp_f32_e32 v8, v8
	s_nop 0
	v_mul_f32_e32 v6, v6, v8
	v_mul_f32_e32 v6, v6, v76
	v_mul_f32_e32 v9, 0x3e000000, v6
	v_mul_f32_e32 v6, 0x3c800000, v81
	v_mul_f32_e32 v8, 0xbfb8aa3b, v6
	v_exp_f32_e32 v8, v8
	s_nop 0
	v_add_f32_e32 v8, 1.0, v8
	v_rcp_f32_e32 v8, v8
	s_nop 0
	v_mul_f32_e32 v6, v6, v8
	v_mul_f32_e32 v6, v6, v77
	v_mul_f32_e32 v10, 0x3e000000, v6
	v_mul_f32_e32 v6, 0x3c800000, v70
	v_mul_f32_e32 v8, 0xbfb8aa3b, v6
	v_exp_f32_e32 v8, v8
	s_nop 0
	v_add_f32_e32 v8, 1.0, v8
	v_rcp_f32_e32 v8, v8
	s_nop 0
	v_mul_f32_e32 v6, v6, v8
	v_mul_f32_e32 v6, v6, v66
	v_mul_f32_e32 v11, 0x3e000000, v6
	v_mul_f32_e32 v6, 0x3c800000, v71
	v_mul_f32_e32 v8, 0xbfb8aa3b, v6
	v_exp_f32_e32 v8, v8
	s_nop 0
	v_add_f32_e32 v8, 1.0, v8
	v_rcp_f32_e32 v8, v8
	s_nop 0
	v_mul_f32_e32 v6, v6, v8
	v_mul_f32_e32 v6, v6, v67
	v_mul_f32_e32 v12, 0x3e000000, v6
	v_mul_f32_e32 v6, 0x3c800000, v72
	v_mul_f32_e32 v8, 0xbfb8aa3b, v6
	v_exp_f32_e32 v8, v8
	s_nop 0
	v_add_f32_e32 v8, 1.0, v8
	v_rcp_f32_e32 v8, v8
	s_nop 0
	v_mul_f32_e32 v6, v6, v8
	v_mul_f32_e32 v6, v6, v68
	v_mul_f32_e32 v13, 0x3e000000, v6
	v_mul_f32_e32 v6, 0x3c800000, v73
	v_mul_f32_e32 v8, 0xbfb8aa3b, v6
	v_exp_f32_e32 v8, v8
	s_nop 0
	v_add_f32_e32 v8, 1.0, v8
	v_rcp_f32_e32 v8, v8
	s_nop 0
	v_mul_f32_e32 v6, v6, v8
	v_mov_b32_e32 v8, v163
	v_cvt_pk_fp8_f32 v8, v5, v7
	v_med3_f32 v5, v9, s40, v190
	v_med3_f32 v7, v10, s40, v190
	v_mov_b32_e32 v9, v163
	v_cvt_pk_fp8_f32 v8, v5, v7 op_sel:[0,0,1]
	v_med3_f32 v5, v11, s40, v190
	v_med3_f32 v7, v12, s40, v190
	v_cvt_pk_fp8_f32 v9, v5, v7
	v_mul_f32_e32 v6, v6, v69
	v_mul_f32_e32 v14, 0x3e000000, v6
	v_add_u32_e32 v6, 0x90, v4
	v_med3_f32 v5, v13, s40, v190
	v_med3_f32 v7, v14, s40, v190
	v_cvt_pk_fp8_f32 v9, v5, v7 op_sel:[0,0,1]
	v_ashrrev_i32_e32 v7, 31, v6
	v_lshlrev_b64 v[6:7], 7, v[6:7]
	v_lshl_add_u64 v[6:7], s[12:13], 0, v[6:7]
	v_lshl_add_u64 v[6:7], v[6:7], 0, v[2:3]
	v_mul_f32_e32 v5, 0x3c800000, v62
	global_store_dwordx2 v[6:7], v[8:9], off
	v_mul_f32_e32 v6, 0xbfb8aa3b, v5
	v_exp_f32_e32 v6, v6
	s_nop 0
	v_add_f32_e32 v6, 1.0, v6
	v_rcp_f32_e32 v6, v6
	s_nop 0
	v_mul_f32_e32 v5, v5, v6
	v_mul_f32_e32 v6, 0x3c800000, v63
	v_mul_f32_e32 v7, 0xbfb8aa3b, v6
	v_exp_f32_e32 v7, v7
	v_mul_f32_e32 v5, v5, v58
	v_mul_f32_e32 v5, 0x3e000000, v5
	v_med3_f32 v5, v5, s40, v190
	v_add_f32_e32 v7, 1.0, v7
	v_rcp_f32_e32 v7, v7
	s_nop 0
	v_mul_f32_e32 v6, v6, v7
	v_mul_f32_e32 v6, v6, v59
	v_mul_f32_e32 v7, 0x3e000000, v6
	v_mul_f32_e32 v6, 0x3c800000, v64
	v_mul_f32_e32 v8, 0xbfb8aa3b, v6
	v_exp_f32_e32 v8, v8
	v_med3_f32 v7, v7, s40, v190
	v_add_f32_e32 v8, 1.0, v8
	v_rcp_f32_e32 v8, v8
	s_nop 0
	v_mul_f32_e32 v6, v6, v8
	v_mul_f32_e32 v6, v6, v60
	v_mul_f32_e32 v9, 0x3e000000, v6
	v_mul_f32_e32 v6, 0x3c800000, v65
	v_mul_f32_e32 v8, 0xbfb8aa3b, v6
	v_exp_f32_e32 v8, v8
	s_nop 0
	v_add_f32_e32 v8, 1.0, v8
	v_rcp_f32_e32 v8, v8
	s_nop 0
	v_mul_f32_e32 v6, v6, v8
	v_mul_f32_e32 v6, v6, v61
	v_mul_f32_e32 v10, 0x3e000000, v6
	v_mul_f32_e32 v6, 0x3c800000, v54
	v_mul_f32_e32 v8, 0xbfb8aa3b, v6
	v_exp_f32_e32 v8, v8
	s_nop 0
	v_add_f32_e32 v8, 1.0, v8
	v_rcp_f32_e32 v8, v8
	s_nop 0
	v_mul_f32_e32 v6, v6, v8
	v_mul_f32_e32 v6, v6, v50
	v_mul_f32_e32 v11, 0x3e000000, v6
	v_mul_f32_e32 v6, 0x3c800000, v55
	v_mul_f32_e32 v8, 0xbfb8aa3b, v6
	v_exp_f32_e32 v8, v8
	s_nop 0
	v_add_f32_e32 v8, 1.0, v8
	v_rcp_f32_e32 v8, v8
	s_nop 0
	v_mul_f32_e32 v6, v6, v8
	v_mul_f32_e32 v6, v6, v51
	v_mul_f32_e32 v12, 0x3e000000, v6
	v_mul_f32_e32 v6, 0x3c800000, v56
	v_mul_f32_e32 v8, 0xbfb8aa3b, v6
	v_exp_f32_e32 v8, v8
	s_nop 0
	v_add_f32_e32 v8, 1.0, v8
	v_rcp_f32_e32 v8, v8
	s_nop 0
	v_mul_f32_e32 v6, v6, v8
	v_mul_f32_e32 v6, v6, v52
	v_mul_f32_e32 v13, 0x3e000000, v6
	v_mul_f32_e32 v6, 0x3c800000, v57
	v_mul_f32_e32 v8, 0xbfb8aa3b, v6
	v_exp_f32_e32 v8, v8
	s_nop 0
	v_add_f32_e32 v8, 1.0, v8
	v_rcp_f32_e32 v8, v8
	s_nop 0
	v_mul_f32_e32 v6, v6, v8
	v_mov_b32_e32 v8, v163
	v_cvt_pk_fp8_f32 v8, v5, v7
	v_med3_f32 v5, v9, s40, v190
	v_med3_f32 v7, v10, s40, v190
	v_mov_b32_e32 v9, v163
	v_cvt_pk_fp8_f32 v8, v5, v7 op_sel:[0,0,1]
	v_med3_f32 v5, v11, s40, v190
	v_med3_f32 v7, v12, s40, v190
	v_cvt_pk_fp8_f32 v9, v5, v7
	v_mul_f32_e32 v6, v6, v53
	v_mul_f32_e32 v14, 0x3e000000, v6
	v_add_u32_e32 v6, 0xa0, v4
	v_med3_f32 v5, v13, s40, v190
	v_med3_f32 v7, v14, s40, v190
	v_cvt_pk_fp8_f32 v9, v5, v7 op_sel:[0,0,1]
	v_ashrrev_i32_e32 v7, 31, v6
	v_lshlrev_b64 v[6:7], 7, v[6:7]
	v_lshl_add_u64 v[6:7], s[12:13], 0, v[6:7]
	v_lshl_add_u64 v[6:7], v[6:7], 0, v[2:3]
	v_mul_f32_e32 v5, 0x3c800000, v46
	global_store_dwordx2 v[6:7], v[8:9], off
	v_mul_f32_e32 v6, 0xbfb8aa3b, v5
	v_exp_f32_e32 v6, v6
	v_add_u32_e32 v4, 0xb0, v4
	v_add_f32_e32 v6, 1.0, v6
	v_rcp_f32_e32 v6, v6
	s_nop 0
	v_mul_f32_e32 v5, v5, v6
	v_mul_f32_e32 v6, 0x3c800000, v47
	v_mul_f32_e32 v7, 0xbfb8aa3b, v6
	v_exp_f32_e32 v7, v7
	v_mul_f32_e32 v5, v5, v42
	v_mul_f32_e32 v5, 0x3e000000, v5
	v_med3_f32 v5, v5, s40, v190
	v_add_f32_e32 v7, 1.0, v7
	v_rcp_f32_e32 v7, v7
	s_nop 0
	v_mul_f32_e32 v6, v6, v7
	v_mul_f32_e32 v7, 0x3c800000, v48
	v_mul_f32_e32 v8, 0xbfb8aa3b, v7
	v_exp_f32_e32 v8, v8
	v_mul_f32_e32 v6, v6, v43
	v_mul_f32_e32 v6, 0x3e000000, v6
	v_add_f32_e32 v8, 1.0, v8
	v_rcp_f32_e32 v8, v8
	s_nop 0
	v_mul_f32_e32 v7, v7, v8
	v_mul_f32_e32 v8, 0x3c800000, v49
	v_mul_f32_e32 v9, 0xbfb8aa3b, v8
	v_exp_f32_e32 v9, v9
	v_mul_f32_e32 v7, v7, v44
	v_mul_f32_e32 v7, 0x3e000000, v7
	v_add_f32_e32 v9, 1.0, v9
	v_rcp_f32_e32 v9, v9
	s_nop 0
	v_mul_f32_e32 v8, v8, v9
	v_mul_f32_e32 v9, 0x3c800000, v38
	v_mul_f32_e32 v10, 0xbfb8aa3b, v9
	v_exp_f32_e32 v10, v10
	v_mul_f32_e32 v8, v8, v45
	v_mul_f32_e32 v8, 0x3e000000, v8
	v_add_f32_e32 v10, 1.0, v10
	v_rcp_f32_e32 v10, v10
	s_nop 0
	v_mul_f32_e32 v9, v9, v10
	v_mul_f32_e32 v10, 0x3c800000, v39
	v_mul_f32_e32 v11, 0xbfb8aa3b, v10
	v_exp_f32_e32 v11, v11
	v_mul_f32_e32 v9, v9, v34
	v_mul_f32_e32 v9, 0x3e000000, v9
	v_add_f32_e32 v11, 1.0, v11
	v_rcp_f32_e32 v11, v11
	s_nop 0
	v_mul_f32_e32 v10, v10, v11
	v_mul_f32_e32 v11, 0x3c800000, v40
	v_mul_f32_e32 v12, 0xbfb8aa3b, v11
	v_exp_f32_e32 v12, v12
	v_mul_f32_e32 v10, v10, v35
	v_mul_f32_e32 v10, 0x3e000000, v10
	v_add_f32_e32 v12, 1.0, v12
	v_rcp_f32_e32 v12, v12
	s_nop 0
	v_mul_f32_e32 v11, v11, v12
	v_mul_f32_e32 v12, 0x3c800000, v41
	v_mul_f32_e32 v13, 0xbfb8aa3b, v12
	v_exp_f32_e32 v13, v13
	v_mul_f32_e32 v11, v11, v36
	v_mul_f32_e32 v11, 0x3e000000, v11
	v_add_f32_e32 v13, 1.0, v13
	v_rcp_f32_e32 v13, v13
	s_nop 0
	v_mul_f32_e32 v12, v12, v13
	v_med3_f32 v13, v6, s40, v190
	v_mov_b32_e32 v6, v163
	v_cvt_pk_fp8_f32 v6, v5, v13
	v_med3_f32 v5, v7, s40, v190
	v_med3_f32 v7, v8, s40, v190
	v_med3_f32 v8, v10, s40, v190
	v_cvt_pk_fp8_f32 v6, v5, v7 op_sel:[0,0,1]
	v_med3_f32 v5, v9, s40, v190
	v_mov_b32_e32 v7, v163
	v_cvt_pk_fp8_f32 v7, v5, v8
	v_mul_f32_e32 v12, v12, v37
	v_mul_f32_e32 v12, 0x3e000000, v12
	v_med3_f32 v5, v11, s40, v190
	v_med3_f32 v8, v12, s40, v190
	v_cvt_pk_fp8_f32 v7, v5, v8 op_sel:[0,0,1]
	v_ashrrev_i32_e32 v5, 31, v4
	v_lshlrev_b64 v[4:5], 7, v[4:5]
	v_lshl_add_u64 v[4:5], s[12:13], 0, v[4:5]
	v_lshl_add_u64 v[2:3], v[4:5], 0, v[2:3]
	global_store_dwordx2 v[2:3], v[6:7], off
	s_cbranch_vccz .LBB0_1291
	s_waitcnt vmcnt(0)
	s_cmpk_gt_u32 s42, 0xff
	s_cbranch_scc1 .LBB0_1237
	s_barrier
	s_branch .LBB0_1237

.LBB0_1369:
	ds_read_b128 v[2:5], v169
	ds_read_b128 v[6:9], v169 offset:1024
	ds_read_b128 v[10:13], v169 offset:2048
	ds_read_b128 v[14:17], v169 offset:3072
	s_add_u32 s0, s28, 0x4000
	s_addc_u32 s1, s29, 0
	s_cmp_eq_u32 s53, 4
	s_cselect_b32 s36, s49, s0
	s_cselect_b32 s37, s21, s1
	s_cselect_b32 s30, s50, s51
	s_cselect_b32 s31, s19, s52
	s_add_u32 s34, s36, 0x8000
	s_addc_u32 s35, s37, 0
	v_lshl_add_u64 v[162:163], s[28:29], 0, v[156:157]
	s_add_i32 m0, s17, 0xc000
	ds_read_b128 v[174:177], v170
	ds_read_b128 v[178:181], v170 offset:1024
	ds_read_b128 v[182:185], v170 offset:2048
	ds_read_b128 v[186:189], v170 offset:3072
	ds_read_b128 v[190:193], v170 offset:4096
	ds_read_b128 v[194:197], v170 offset:5120
	ds_read_b128 v[198:201], v170 offset:6144
	ds_read_b128 v[202:205], v170 offset:7168
	global_load_lds_dwordx4 v[162:163], off
	v_lshl_add_u64 v[162:163], s[28:29], 0, v[154:155]
	s_add_i32 m0, s17, 0xe000
	s_nop 0
	global_load_lds_dwordx4 v[162:163], off
	s_waitcnt lgkmcnt(8)
	s_waitcnt vmcnt(10)
	s_barrier
	s_waitcnt lgkmcnt(0)
	s_waitcnt lgkmcnt(0)
	v_mfma_scale_f32_16x16x128_f8f6f4 v[142:145], v[2:9], v[174:181], v[142:145], v171, v171 op_sel_hi:[0,0,0]
	v_mfma_scale_f32_16x16x128_f8f6f4 v[138:141], v[10:17], v[174:181], v[138:141], v171, v171 op_sel_hi:[0,0,0]
	v_mfma_scale_f32_16x16x128_f8f6f4 v[126:129], v[2:9], v[182:189], v[126:129], v171, v171 op_sel_hi:[0,0,0]
	v_mfma_scale_f32_16x16x128_f8f6f4 v[122:125], v[10:17], v[182:189], v[122:125], v171, v171 op_sel_hi:[0,0,0]
	v_mfma_scale_f32_16x16x128_f8f6f4 v[110:113], v[2:9], v[190:197], v[110:113], v171, v171 op_sel_hi:[0,0,0]
	v_mfma_scale_f32_16x16x128_f8f6f4 v[106:109], v[10:17], v[190:197], v[106:109], v171, v171 op_sel_hi:[0,0,0]
	v_mfma_scale_f32_16x16x128_f8f6f4 v[94:97], v[2:9], v[198:205], v[94:97], v171, v171 op_sel_hi:[0,0,0]
	v_mfma_scale_f32_16x16x128_f8f6f4 v[90:93], v[10:17], v[198:205], v[90:93], v171, v171 op_sel_hi:[0,0,0]
	s_barrier
	s_add_i32 s0, s45, s11
	v_lshl_add_u64 v[162:163], s[30:31], 0, v[150:151]
	s_mov_b32 m0, s0
	ds_read_b128 v[206:209], v172
	ds_read_b128 v[210:213], v172 offset:1024
	ds_read_b128 v[214:217], v172 offset:2048
	ds_read_b128 v[218:221], v172 offset:3072
	global_load_lds_dwordx4 v[162:163], off
	v_lshl_add_u64 v[164:165], s[30:31], 0, v[146:147]
	s_add_i32 m0, s0, 0x2000
	s_nop 0
	global_load_lds_dwordx4 v[164:165], off
	s_waitcnt vmcnt(10)
	s_barrier
	s_waitcnt lgkmcnt(0)
	s_waitcnt lgkmcnt(0)
	v_mfma_scale_f32_16x16x128_f8f6f4 v[134:137], v[206:213], v[174:181], v[134:137], v171, v171 op_sel_hi:[0,0,0]
	v_mfma_scale_f32_16x16x128_f8f6f4 v[130:133], v[214:221], v[174:181], v[130:133], v171, v171 op_sel_hi:[0,0,0]
	v_mfma_scale_f32_16x16x128_f8f6f4 v[118:121], v[206:213], v[182:189], v[118:121], v171, v171 op_sel_hi:[0,0,0]
	v_mfma_scale_f32_16x16x128_f8f6f4 v[114:117], v[214:221], v[182:189], v[114:117], v171, v171 op_sel_hi:[0,0,0]
	v_mfma_scale_f32_16x16x128_f8f6f4 v[102:105], v[206:213], v[190:197], v[102:105], v171, v171 op_sel_hi:[0,0,0]
	v_mfma_scale_f32_16x16x128_f8f6f4 v[98:101], v[214:221], v[190:197], v[98:101], v171, v171 op_sel_hi:[0,0,0]
	v_mfma_scale_f32_16x16x128_f8f6f4 v[86:89], v[206:213], v[198:205], v[86:89], v171, v171 op_sel_hi:[0,0,0]
	v_mfma_scale_f32_16x16x128_f8f6f4 v[82:85], v[214:221], v[198:205], v[82:85], v171, v171 op_sel_hi:[0,0,0]
	s_mov_b32 m0, s17
	v_lshl_add_u64 v[222:223], s[36:37], 0, v[152:153]
	s_barrier
	ds_read_b128 v[174:177], v170 offset:16384
	ds_read_b128 v[178:181], v170 offset:17408
	ds_read_b128 v[182:185], v170 offset:18432
	ds_read_b128 v[186:189], v170 offset:19456
	ds_read_b128 v[190:193], v170 offset:20480
	ds_read_b128 v[194:197], v170 offset:21504
	ds_read_b128 v[198:201], v170 offset:22528
	ds_read_b128 v[202:205], v170 offset:23552
	global_load_lds_dwordx4 v[222:223], off
	v_lshl_add_u64 v[222:223], s[36:37], 0, v[148:149]
	s_mov_b32 m0, s27
	s_nop 0
	global_load_lds_dwordx4 v[222:223], off
	s_waitcnt vmcnt(10)
	s_barrier
	s_waitcnt lgkmcnt(0)
	s_waitcnt lgkmcnt(0)
	v_mfma_scale_f32_16x16x128_f8f6f4 v[78:81], v[2:9], v[174:181], v[78:81], v171, v171 op_sel_hi:[0,0,0]
	v_mfma_scale_f32_16x16x128_f8f6f4 v[74:77], v[10:17], v[174:181], v[74:77], v171, v171 op_sel_hi:[0,0,0]
	v_mfma_scale_f32_16x16x128_f8f6f4 v[62:65], v[2:9], v[182:189], v[62:65], v171, v171 op_sel_hi:[0,0,0]
	v_mfma_scale_f32_16x16x128_f8f6f4 v[58:61], v[10:17], v[182:189], v[58:61], v171, v171 op_sel_hi:[0,0,0]
	v_mfma_scale_f32_16x16x128_f8f6f4 v[46:49], v[2:9], v[190:197], v[46:49], v171, v171 op_sel_hi:[0,0,0]
	v_mfma_scale_f32_16x16x128_f8f6f4 v[42:45], v[10:17], v[190:197], v[42:45], v171, v171 op_sel_hi:[0,0,0]
	v_mfma_scale_f32_16x16x128_f8f6f4 v[30:33], v[2:9], v[198:205], v[30:33], v171, v171 op_sel_hi:[0,0,0]
	v_mfma_scale_f32_16x16x128_f8f6f4 v[26:29], v[10:17], v[198:205], v[26:29], v171, v171 op_sel_hi:[0,0,0]
	s_barrier
	s_add_u32 s0, s30, 0x20000
	s_addc_u32 s1, s31, 0
	s_add_i32 s54, s46, s11
	v_lshl_add_u64 v[2:3], s[0:1], 0, v[150:151]
	s_mov_b32 m0, s54
	s_nop 0
	global_load_lds_dwordx4 v[2:3], off
	v_lshl_add_u64 v[2:3], s[0:1], 0, v[146:147]
	s_add_i32 m0, s54, 0x2000
	s_nop 0
	global_load_lds_dwordx4 v[2:3], off
	s_waitcnt vmcnt(10)
	s_barrier
	v_mfma_scale_f32_16x16x128_f8f6f4 v[70:73], v[206:213], v[174:181], v[70:73], v171, v171 op_sel_hi:[0,0,0]
	v_mfma_scale_f32_16x16x128_f8f6f4 v[66:69], v[214:221], v[174:181], v[66:69], v171, v171 op_sel_hi:[0,0,0]
	v_mfma_scale_f32_16x16x128_f8f6f4 v[54:57], v[206:213], v[182:189], v[54:57], v171, v171 op_sel_hi:[0,0,0]
	v_mfma_scale_f32_16x16x128_f8f6f4 v[50:53], v[214:221], v[182:189], v[50:53], v171, v171 op_sel_hi:[0,0,0]
	v_mfma_scale_f32_16x16x128_f8f6f4 v[38:41], v[206:213], v[190:197], v[38:41], v171, v171 op_sel_hi:[0,0,0]
	v_mfma_scale_f32_16x16x128_f8f6f4 v[34:37], v[214:221], v[190:197], v[34:37], v171, v171 op_sel_hi:[0,0,0]
	v_mfma_scale_f32_16x16x128_f8f6f4 v[22:25], v[206:213], v[198:205], v[22:25], v171, v171 op_sel_hi:[0,0,0]
	v_mfma_scale_f32_16x16x128_f8f6f4 v[18:21], v[214:221], v[198:205], v[18:21], v171, v171 op_sel_hi:[0,0,0]
	s_add_i32 s54, 0, 0x18000
	v_add_u32_e32 v14, s54, v168
	s_barrier
	ds_read_b128 v[2:5], v14
	ds_read_b128 v[6:9], v14 offset:1024
	ds_read_b128 v[10:13], v14 offset:2048
	ds_read_b128 v[14:17], v14 offset:3072
	s_add_u32 s0, s36, 0x4000
	s_addc_u32 s1, s37, 0
	s_mov_b32 m0, s38
	v_lshl_add_u64 v[206:207], s[0:1], 0, v[152:153]
	ds_read_b128 v[174:177], v170 offset:32768
	ds_read_b128 v[178:181], v170 offset:33792
	ds_read_b128 v[182:185], v170 offset:34816
	ds_read_b128 v[186:189], v170 offset:35840
	ds_read_b128 v[190:193], v170 offset:36864
	ds_read_b128 v[194:197], v170 offset:37888
	ds_read_b128 v[198:201], v170 offset:38912
	ds_read_b128 v[202:205], v170 offset:39936
	global_load_lds_dwordx4 v[206:207], off
	v_lshl_add_u64 v[206:207], s[0:1], 0, v[148:149]
	s_mov_b32 m0, s39
	s_nop 0
	global_load_lds_dwordx4 v[206:207], off
	s_waitcnt lgkmcnt(8)
	s_waitcnt vmcnt(10)
	s_barrier
	s_waitcnt lgkmcnt(0)
	s_waitcnt lgkmcnt(0)
	v_mfma_scale_f32_16x16x128_f8f6f4 v[142:145], v[2:9], v[174:181], v[142:145], v171, v171 op_sel_hi:[0,0,0]
	v_mfma_scale_f32_16x16x128_f8f6f4 v[138:141], v[10:17], v[174:181], v[138:141], v171, v171 op_sel_hi:[0,0,0]
	v_mfma_scale_f32_16x16x128_f8f6f4 v[126:129], v[2:9], v[182:189], v[126:129], v171, v171 op_sel_hi:[0,0,0]
	v_mfma_scale_f32_16x16x128_f8f6f4 v[122:125], v[10:17], v[182:189], v[122:125], v171, v171 op_sel_hi:[0,0,0]
	v_mfma_scale_f32_16x16x128_f8f6f4 v[110:113], v[2:9], v[190:197], v[110:113], v171, v171 op_sel_hi:[0,0,0]
	v_mfma_scale_f32_16x16x128_f8f6f4 v[106:109], v[10:17], v[190:197], v[106:109], v171, v171 op_sel_hi:[0,0,0]
	v_mfma_scale_f32_16x16x128_f8f6f4 v[94:97], v[2:9], v[198:205], v[94:97], v171, v171 op_sel_hi:[0,0,0]
	v_mfma_scale_f32_16x16x128_f8f6f4 v[90:93], v[10:17], v[198:205], v[90:93], v171, v171 op_sel_hi:[0,0,0]
	s_barrier
	s_add_i32 s36, 0, 0x1c000
	s_add_i32 s0, s54, s11
	v_add_u32_e32 v218, s36, v168
	v_lshl_add_u64 v[162:163], v[162:163], 0, s[14:15]
	s_mov_b32 m0, s0
	ds_read_b128 v[206:209], v218
	ds_read_b128 v[210:213], v218 offset:1024
	ds_read_b128 v[214:217], v218 offset:2048
	ds_read_b128 v[218:221], v218 offset:3072
	global_load_lds_dwordx4 v[162:163], off
	v_lshl_add_u64 v[162:163], v[164:165], 0, s[14:15]
	s_add_i32 m0, s0, 0x2000
	s_nop 0
	global_load_lds_dwordx4 v[162:163], off
	s_waitcnt vmcnt(10)
	s_barrier
	s_waitcnt lgkmcnt(0)
	s_waitcnt lgkmcnt(0)
	v_mfma_scale_f32_16x16x128_f8f6f4 v[134:137], v[206:213], v[174:181], v[134:137], v171, v171 op_sel_hi:[0,0,0]
	v_mfma_scale_f32_16x16x128_f8f6f4 v[130:133], v[214:221], v[174:181], v[130:133], v171, v171 op_sel_hi:[0,0,0]
	v_mfma_scale_f32_16x16x128_f8f6f4 v[118:121], v[206:213], v[182:189], v[118:121], v171, v171 op_sel_hi:[0,0,0]
	v_mfma_scale_f32_16x16x128_f8f6f4 v[114:117], v[214:221], v[182:189], v[114:117], v171, v171 op_sel_hi:[0,0,0]
	v_mfma_scale_f32_16x16x128_f8f6f4 v[102:105], v[206:213], v[190:197], v[102:105], v171, v171 op_sel_hi:[0,0,0]
	v_mfma_scale_f32_16x16x128_f8f6f4 v[98:101], v[214:221], v[190:197], v[98:101], v171, v171 op_sel_hi:[0,0,0]
	v_mfma_scale_f32_16x16x128_f8f6f4 v[86:89], v[206:213], v[198:205], v[86:89], v171, v171 op_sel_hi:[0,0,0]
	v_mfma_scale_f32_16x16x128_f8f6f4 v[82:85], v[214:221], v[198:205], v[82:85], v171, v171 op_sel_hi:[0,0,0]
	s_mov_b32 m0, s43
	v_lshl_add_u64 v[162:163], s[34:35], 0, v[152:153]
	s_barrier
	ds_read_b128 v[174:177], v170 offset:49152
	ds_read_b128 v[178:181], v170 offset:50176
	ds_read_b128 v[182:185], v170 offset:51200
	ds_read_b128 v[186:189], v170 offset:52224
	ds_read_b128 v[190:193], v170 offset:53248
	ds_read_b128 v[194:197], v170 offset:54272
	ds_read_b128 v[198:201], v170 offset:55296
	ds_read_b128 v[202:205], v170 offset:56320
	global_load_lds_dwordx4 v[162:163], off
	v_lshl_add_u64 v[162:163], s[34:35], 0, v[148:149]
	s_mov_b32 m0, s44
	s_nop 0
	global_load_lds_dwordx4 v[162:163], off
	s_waitcnt vmcnt(10)
	s_barrier
	s_waitcnt lgkmcnt(0)
	s_waitcnt lgkmcnt(0)
	v_mfma_scale_f32_16x16x128_f8f6f4 v[78:81], v[2:9], v[174:181], v[78:81], v171, v171 op_sel_hi:[0,0,0]
	v_mfma_scale_f32_16x16x128_f8f6f4 v[74:77], v[10:17], v[174:181], v[74:77], v171, v171 op_sel_hi:[0,0,0]
	v_mfma_scale_f32_16x16x128_f8f6f4 v[62:65], v[2:9], v[182:189], v[62:65], v171, v171 op_sel_hi:[0,0,0]
	v_mfma_scale_f32_16x16x128_f8f6f4 v[58:61], v[10:17], v[182:189], v[58:61], v171, v171 op_sel_hi:[0,0,0]
	v_mfma_scale_f32_16x16x128_f8f6f4 v[46:49], v[2:9], v[190:197], v[46:49], v171, v171 op_sel_hi:[0,0,0]
	v_mfma_scale_f32_16x16x128_f8f6f4 v[42:45], v[10:17], v[190:197], v[42:45], v171, v171 op_sel_hi:[0,0,0]
	v_mfma_scale_f32_16x16x128_f8f6f4 v[30:33], v[2:9], v[198:205], v[30:33], v171, v171 op_sel_hi:[0,0,0]
	v_mfma_scale_f32_16x16x128_f8f6f4 v[26:29], v[10:17], v[198:205], v[26:29], v171, v171 op_sel_hi:[0,0,0]
	s_barrier
	s_add_u32 s0, s30, 0x20080
	s_addc_u32 s1, s31, 0
	s_add_i32 s30, s36, s11
	v_lshl_add_u64 v[2:3], s[0:1], 0, v[150:151]
	s_mov_b32 m0, s30
	s_nop 0
	global_load_lds_dwordx4 v[2:3], off
	v_lshl_add_u64 v[2:3], s[0:1], 0, v[146:147]
	s_add_i32 m0, s30, 0x2000
	s_nop 0
	global_load_lds_dwordx4 v[2:3], off
	s_waitcnt vmcnt(10)
	s_barrier
	v_mfma_scale_f32_16x16x128_f8f6f4 v[70:73], v[206:213], v[174:181], v[70:73], v171, v171 op_sel_hi:[0,0,0]
	v_mfma_scale_f32_16x16x128_f8f6f4 v[66:69], v[214:221], v[174:181], v[66:69], v171, v171 op_sel_hi:[0,0,0]
	v_mfma_scale_f32_16x16x128_f8f6f4 v[54:57], v[206:213], v[182:189], v[54:57], v171, v171 op_sel_hi:[0,0,0]
	v_mfma_scale_f32_16x16x128_f8f6f4 v[50:53], v[214:221], v[182:189], v[50:53], v171, v171 op_sel_hi:[0,0,0]
	v_mfma_scale_f32_16x16x128_f8f6f4 v[38:41], v[206:213], v[190:197], v[38:41], v171, v171 op_sel_hi:[0,0,0]
	v_mfma_scale_f32_16x16x128_f8f6f4 v[34:37], v[214:221], v[190:197], v[34:37], v171, v171 op_sel_hi:[0,0,0]
	v_mfma_scale_f32_16x16x128_f8f6f4 v[22:25], v[206:213], v[198:205], v[22:25], v171, v171 op_sel_hi:[0,0,0]
	v_mfma_scale_f32_16x16x128_f8f6f4 v[18:21], v[214:221], v[198:205], v[18:21], v171, v171 op_sel_hi:[0,0,0]
	s_add_i32 s53, s53, 2
	s_add_u32 s51, s51, 0x100
	s_addc_u32 s52, s52, 0
	s_add_u32 s28, s28, 0x10000
	s_addc_u32 s29, s29, 0
	s_cmp_gt_u32 s53, 5
	s_barrier
	s_cbranch_scc0 .LBB0_1369
	v_pk_mul_f32 v[10:11], v[142:143], s[16:17] op_sel_hi:[1,0]
	v_pk_mul_f32 v[8:9], v[144:145], s[16:17] op_sel_hi:[1,0]
	v_med3_f32 v5, v10, s47, v173
	v_med3_f32 v11, v11, s47, v173
	v_mov_b32_e32 v10, 0
	v_cvt_pk_fp8_f32 v10, v5, v11
	v_mov_b32_e32 v3, v166
	v_mov_b32_e32 v2, v167
	s_lshl_b32 s0, s48, 8
	v_pk_mul_f32 v[14:15], v[138:139], s[16:17] op_sel_hi:[1,0]
	v_med3_f32 v5, v8, s47, v173
	v_med3_f32 v8, v9, s47, v173
	s_nop 15
	s_nop 15
	s_or_b32 s0, s0, s42
	v_cvt_pk_fp8_f32 v10, v5, v8 op_sel:[0,0,1]
	v_med3_f32 v5, v14, s47, v173
	v_med3_f32 v8, v15, s47, v173
	v_mov_b32_e32 v11, 0
	v_lshl_add_u32 v2, v2, 3, s0
	s_lshl_b32 s0, s26, 8
	v_cvt_pk_fp8_f32 v11, v5, v8
	s_add_i32 s0, s0, s41
	v_add_u32_e32 v4, s0, v3
	v_pk_mul_f32 v[12:13], v[140:141], s[16:17] op_sel_hi:[1,0]
	v_mov_b32_e32 v6, v4
	v_med3_f32 v5, v12, s47, v173
	v_med3_f32 v8, v13, s47, v173
	v_cvt_pk_fp8_f32 v11, v5, v8 op_sel:[0,0,1]
	v_ashrrev_i32_e32 v7, 31, v6
	v_lshlrev_b64 v[6:7], 10, v[6:7]
	v_ashrrev_i32_e32 v3, 31, v2
	v_lshl_add_u64 v[6:7], s[12:13], 0, v[6:7]
	v_lshl_add_u64 v[6:7], v[6:7], 0, v[2:3]
	global_store_dwordx2 v[6:7], v[10:11], off
	v_pk_mul_f32 v[10:11], v[134:135], s[16:17] op_sel_hi:[1,0]
	v_pk_mul_f32 v[8:9], v[136:137], s[16:17] op_sel_hi:[1,0]
	v_med3_f32 v5, v10, s47, v173
	v_med3_f32 v11, v11, s47, v173
	v_mov_b32_e32 v10, 0
	v_cvt_pk_fp8_f32 v10, v5, v11
	v_pk_mul_f32 v[14:15], v[130:131], s[16:17] op_sel_hi:[1,0]
	v_med3_f32 v5, v8, s47, v173
	v_med3_f32 v8, v9, s47, v173
	v_cvt_pk_fp8_f32 v10, v5, v8 op_sel:[0,0,1]
	v_med3_f32 v5, v14, s47, v173
	v_med3_f32 v8, v15, s47, v173
	v_mov_b32_e32 v11, 0
	v_cvt_pk_fp8_f32 v11, v5, v8
	v_pk_mul_f32 v[12:13], v[132:133], s[16:17] op_sel_hi:[1,0]
	v_pk_mul_f32 v[14:15], v[122:123], s[16:17] op_sel_hi:[1,0]
	v_med3_f32 v5, v12, s47, v173
	v_med3_f32 v8, v13, s47, v173
	v_cvt_pk_fp8_f32 v11, v5, v8 op_sel:[0,0,1]
	v_pk_mul_f32 v[8:9], v[128:129], s[16:17] op_sel_hi:[1,0]
	v_pk_mul_f32 v[12:13], v[124:125], s[16:17] op_sel_hi:[1,0]
	s_and_b64 vcc, exec, s[8:9]
	global_store_dwordx2 v[6:7], v[10:11], off offset:128
	v_pk_mul_f32 v[10:11], v[126:127], s[16:17] op_sel_hi:[1,0]
	v_add_u32_e32 v6, 16, v4
	v_med3_f32 v5, v10, s47, v173
	v_med3_f32 v11, v11, s47, v173
	v_mov_b32_e32 v10, 0
	v_cvt_pk_fp8_f32 v10, v5, v11
	v_med3_f32 v5, v8, s47, v173
	v_med3_f32 v8, v9, s47, v173
	v_mov_b32_e32 v11, 0
	v_cvt_pk_fp8_f32 v10, v5, v8 op_sel:[0,0,1]
	v_med3_f32 v5, v14, s47, v173
	v_med3_f32 v8, v15, s47, v173
	v_cvt_pk_fp8_f32 v11, v5, v8
	v_med3_f32 v5, v12, s47, v173
	v_med3_f32 v8, v13, s47, v173
	v_cvt_pk_fp8_f32 v11, v5, v8 op_sel:[0,0,1]
	v_ashrrev_i32_e32 v7, 31, v6
	v_lshlrev_b64 v[6:7], 10, v[6:7]
	v_lshl_add_u64 v[6:7], s[12:13], 0, v[6:7]
	v_lshl_add_u64 v[6:7], v[6:7], 0, v[2:3]
	global_store_dwordx2 v[6:7], v[10:11], off
	v_pk_mul_f32 v[10:11], v[118:119], s[16:17] op_sel_hi:[1,0]
	v_pk_mul_f32 v[8:9], v[120:121], s[16:17] op_sel_hi:[1,0]
	v_med3_f32 v5, v10, s47, v173
	v_med3_f32 v11, v11, s47, v173
	v_mov_b32_e32 v10, 0
	v_cvt_pk_fp8_f32 v10, v5, v11
	v_pk_mul_f32 v[14:15], v[114:115], s[16:17] op_sel_hi:[1,0]
	v_med3_f32 v5, v8, s47, v173
	v_med3_f32 v8, v9, s47, v173
	v_cvt_pk_fp8_f32 v10, v5, v8 op_sel:[0,0,1]
	v_med3_f32 v5, v14, s47, v173
	v_med3_f32 v8, v15, s47, v173
	v_mov_b32_e32 v11, 0
	v_cvt_pk_fp8_f32 v11, v5, v8
	v_pk_mul_f32 v[12:13], v[116:117], s[16:17] op_sel_hi:[1,0]
	v_pk_mul_f32 v[14:15], v[106:107], s[16:17] op_sel_hi:[1,0]
	v_med3_f32 v5, v12, s47, v173
	v_med3_f32 v8, v13, s47, v173
	v_cvt_pk_fp8_f32 v11, v5, v8 op_sel:[0,0,1]
	v_pk_mul_f32 v[8:9], v[112:113], s[16:17] op_sel_hi:[1,0]
	v_pk_mul_f32 v[12:13], v[108:109], s[16:17] op_sel_hi:[1,0]
	s_mov_b32 s48, s18
	global_store_dwordx2 v[6:7], v[10:11], off offset:128
	v_pk_mul_f32 v[10:11], v[110:111], s[16:17] op_sel_hi:[1,0]
	v_add_u32_e32 v6, 32, v4
	v_med3_f32 v5, v10, s47, v173
	v_med3_f32 v11, v11, s47, v173
	v_mov_b32_e32 v10, 0
	v_cvt_pk_fp8_f32 v10, v5, v11
	v_med3_f32 v5, v8, s47, v173
	v_med3_f32 v8, v9, s47, v173
	v_mov_b32_e32 v11, 0
	v_cvt_pk_fp8_f32 v10, v5, v8 op_sel:[0,0,1]
	v_med3_f32 v5, v14, s47, v173
	v_med3_f32 v8, v15, s47, v173
	v_cvt_pk_fp8_f32 v11, v5, v8
	v_med3_f32 v5, v12, s47, v173
	v_med3_f32 v8, v13, s47, v173
	v_cvt_pk_fp8_f32 v11, v5, v8 op_sel:[0,0,1]
	v_ashrrev_i32_e32 v7, 31, v6
	v_lshlrev_b64 v[6:7], 10, v[6:7]
	v_lshl_add_u64 v[6:7], s[12:13], 0, v[6:7]
	v_lshl_add_u64 v[6:7], v[6:7], 0, v[2:3]
	global_store_dwordx2 v[6:7], v[10:11], off
	v_pk_mul_f32 v[10:11], v[102:103], s[16:17] op_sel_hi:[1,0]
	v_pk_mul_f32 v[8:9], v[104:105], s[16:17] op_sel_hi:[1,0]
	v_med3_f32 v5, v10, s47, v173
	v_med3_f32 v11, v11, s47, v173
	v_mov_b32_e32 v10, 0
	v_cvt_pk_fp8_f32 v10, v5, v11
	v_pk_mul_f32 v[14:15], v[98:99], s[16:17] op_sel_hi:[1,0]
	v_med3_f32 v5, v8, s47, v173
	v_med3_f32 v8, v9, s47, v173
	v_cvt_pk_fp8_f32 v10, v5, v8 op_sel:[0,0,1]
	v_med3_f32 v5, v14, s47, v173
	v_med3_f32 v8, v15, s47, v173
	v_mov_b32_e32 v11, 0
	v_cvt_pk_fp8_f32 v11, v5, v8
	v_pk_mul_f32 v[12:13], v[100:101], s[16:17] op_sel_hi:[1,0]
	v_pk_mul_f32 v[14:15], v[90:91], s[16:17] op_sel_hi:[1,0]
	v_med3_f32 v5, v12, s47, v173
	v_med3_f32 v8, v13, s47, v173
	v_cvt_pk_fp8_f32 v11, v5, v8 op_sel:[0,0,1]
	v_pk_mul_f32 v[8:9], v[96:97], s[16:17] op_sel_hi:[1,0]
	v_pk_mul_f32 v[12:13], v[92:93], s[16:17] op_sel_hi:[1,0]
	s_mov_b32 s26, s20
	global_store_dwordx2 v[6:7], v[10:11], off offset:128
	v_pk_mul_f32 v[10:11], v[94:95], s[16:17] op_sel_hi:[1,0]
	v_add_u32_e32 v6, 48, v4
	v_med3_f32 v5, v10, s47, v173
	v_med3_f32 v11, v11, s47, v173
	v_mov_b32_e32 v10, 0
	v_cvt_pk_fp8_f32 v10, v5, v11
	v_med3_f32 v5, v8, s47, v173
	v_med3_f32 v8, v9, s47, v173
	v_mov_b32_e32 v11, 0
	v_cvt_pk_fp8_f32 v10, v5, v8 op_sel:[0,0,1]
	v_med3_f32 v5, v14, s47, v173
	v_med3_f32 v8, v15, s47, v173
	v_cvt_pk_fp8_f32 v11, v5, v8
	v_med3_f32 v5, v12, s47, v173
	v_med3_f32 v8, v13, s47, v173
	v_cvt_pk_fp8_f32 v11, v5, v8 op_sel:[0,0,1]
	v_ashrrev_i32_e32 v7, 31, v6
	v_lshlrev_b64 v[6:7], 10, v[6:7]
	v_lshl_add_u64 v[6:7], s[12:13], 0, v[6:7]
	v_lshl_add_u64 v[6:7], v[6:7], 0, v[2:3]
	global_store_dwordx2 v[6:7], v[10:11], off
	v_pk_mul_f32 v[10:11], v[86:87], s[16:17] op_sel_hi:[1,0]
	v_pk_mul_f32 v[8:9], v[88:89], s[16:17] op_sel_hi:[1,0]
	v_med3_f32 v5, v10, s47, v173
	v_med3_f32 v11, v11, s47, v173
	v_mov_b32_e32 v10, 0
	v_cvt_pk_fp8_f32 v10, v5, v11
	v_pk_mul_f32 v[14:15], v[82:83], s[16:17] op_sel_hi:[1,0]
	v_med3_f32 v5, v8, s47, v173
	v_med3_f32 v8, v9, s47, v173
	v_cvt_pk_fp8_f32 v10, v5, v8 op_sel:[0,0,1]
	v_med3_f32 v5, v14, s47, v173
	v_med3_f32 v8, v15, s47, v173
	v_mov_b32_e32 v11, 0
	v_cvt_pk_fp8_f32 v11, v5, v8
	v_pk_mul_f32 v[12:13], v[84:85], s[16:17] op_sel_hi:[1,0]
	v_pk_mul_f32 v[14:15], v[74:75], s[16:17] op_sel_hi:[1,0]
	v_med3_f32 v5, v12, s47, v173
	v_med3_f32 v8, v13, s47, v173
	v_cvt_pk_fp8_f32 v11, v5, v8 op_sel:[0,0,1]
	v_pk_mul_f32 v[8:9], v[80:81], s[16:17] op_sel_hi:[1,0]
	v_pk_mul_f32 v[12:13], v[76:77], s[16:17] op_sel_hi:[1,0]
	s_mov_b64 s[28:29], s[24:25]
	global_store_dwordx2 v[6:7], v[10:11], off offset:128
	v_pk_mul_f32 v[10:11], v[78:79], s[16:17] op_sel_hi:[1,0]
	v_add_u32_e32 v6, 0x80, v4
	v_med3_f32 v5, v10, s47, v173
	v_med3_f32 v11, v11, s47, v173
	v_mov_b32_e32 v10, 0
	v_cvt_pk_fp8_f32 v10, v5, v11
	v_med3_f32 v5, v8, s47, v173
	v_med3_f32 v8, v9, s47, v173
	v_mov_b32_e32 v11, 0
	v_cvt_pk_fp8_f32 v10, v5, v8 op_sel:[0,0,1]
	v_med3_f32 v5, v14, s47, v173
	v_med3_f32 v8, v15, s47, v173
	v_cvt_pk_fp8_f32 v11, v5, v8
	v_med3_f32 v5, v12, s47, v173
	v_med3_f32 v8, v13, s47, v173
	v_cvt_pk_fp8_f32 v11, v5, v8 op_sel:[0,0,1]
	v_ashrrev_i32_e32 v7, 31, v6
	v_lshlrev_b64 v[6:7], 10, v[6:7]
	v_lshl_add_u64 v[6:7], s[12:13], 0, v[6:7]
	v_lshl_add_u64 v[6:7], v[6:7], 0, v[2:3]
	global_store_dwordx2 v[6:7], v[10:11], off
	v_pk_mul_f32 v[10:11], v[70:71], s[16:17] op_sel_hi:[1,0]
	v_pk_mul_f32 v[8:9], v[72:73], s[16:17] op_sel_hi:[1,0]
	v_med3_f32 v5, v10, s47, v173
	v_med3_f32 v11, v11, s47, v173
	v_mov_b32_e32 v10, 0
	v_cvt_pk_fp8_f32 v10, v5, v11
	v_pk_mul_f32 v[14:15], v[66:67], s[16:17] op_sel_hi:[1,0]
	v_med3_f32 v5, v8, s47, v173
	v_med3_f32 v8, v9, s47, v173
	v_cvt_pk_fp8_f32 v10, v5, v8 op_sel:[0,0,1]
	v_med3_f32 v5, v14, s47, v173
	v_med3_f32 v8, v15, s47, v173
	v_mov_b32_e32 v11, 0
	v_cvt_pk_fp8_f32 v11, v5, v8
	v_pk_mul_f32 v[12:13], v[68:69], s[16:17] op_sel_hi:[1,0]
	v_pk_mul_f32 v[14:15], v[58:59], s[16:17] op_sel_hi:[1,0]
	v_med3_f32 v5, v12, s47, v173
	v_med3_f32 v8, v13, s47, v173
	v_cvt_pk_fp8_f32 v11, v5, v8 op_sel:[0,0,1]
	v_pk_mul_f32 v[8:9], v[64:65], s[16:17] op_sel_hi:[1,0]
	v_pk_mul_f32 v[12:13], v[60:61], s[16:17] op_sel_hi:[1,0]
	s_mov_b64 s[30:31], s[22:23]
	global_store_dwordx2 v[6:7], v[10:11], off offset:128
	v_pk_mul_f32 v[10:11], v[62:63], s[16:17] op_sel_hi:[1,0]
	v_add_u32_e32 v6, 0x90, v4
	v_med3_f32 v5, v10, s47, v173
	v_med3_f32 v11, v11, s47, v173
	v_mov_b32_e32 v10, 0
	v_cvt_pk_fp8_f32 v10, v5, v11
	v_med3_f32 v5, v8, s47, v173
	v_med3_f32 v8, v9, s47, v173
	v_mov_b32_e32 v11, 0
	v_cvt_pk_fp8_f32 v10, v5, v8 op_sel:[0,0,1]
	v_med3_f32 v5, v14, s47, v173
	v_med3_f32 v8, v15, s47, v173
	v_cvt_pk_fp8_f32 v11, v5, v8
	v_med3_f32 v5, v12, s47, v173
	v_med3_f32 v8, v13, s47, v173
	v_cvt_pk_fp8_f32 v11, v5, v8 op_sel:[0,0,1]
	v_ashrrev_i32_e32 v7, 31, v6
	v_lshlrev_b64 v[6:7], 10, v[6:7]
	v_lshl_add_u64 v[6:7], s[12:13], 0, v[6:7]
	v_lshl_add_u64 v[6:7], v[6:7], 0, v[2:3]
	global_store_dwordx2 v[6:7], v[10:11], off
	v_pk_mul_f32 v[10:11], v[54:55], s[16:17] op_sel_hi:[1,0]
	v_pk_mul_f32 v[8:9], v[56:57], s[16:17] op_sel_hi:[1,0]
	v_med3_f32 v5, v10, s47, v173
	v_med3_f32 v11, v11, s47, v173
	v_mov_b32_e32 v10, 0
	v_cvt_pk_fp8_f32 v10, v5, v11
	v_pk_mul_f32 v[14:15], v[50:51], s[16:17] op_sel_hi:[1,0]
	v_med3_f32 v5, v8, s47, v173
	v_med3_f32 v8, v9, s47, v173
	v_cvt_pk_fp8_f32 v10, v5, v8 op_sel:[0,0,1]
	v_med3_f32 v5, v14, s47, v173
	v_med3_f32 v8, v15, s47, v173
	v_mov_b32_e32 v11, 0
	v_cvt_pk_fp8_f32 v11, v5, v8
	v_pk_mul_f32 v[12:13], v[52:53], s[16:17] op_sel_hi:[1,0]
	v_pk_mul_f32 v[14:15], v[42:43], s[16:17] op_sel_hi:[1,0]
	v_med3_f32 v5, v12, s47, v173
	v_med3_f32 v8, v13, s47, v173
	v_cvt_pk_fp8_f32 v11, v5, v8 op_sel:[0,0,1]
	v_pk_mul_f32 v[8:9], v[48:49], s[16:17] op_sel_hi:[1,0]
	v_pk_mul_f32 v[12:13], v[44:45], s[16:17] op_sel_hi:[1,0]
	global_store_dwordx2 v[6:7], v[10:11], off offset:128
	v_pk_mul_f32 v[10:11], v[46:47], s[16:17] op_sel_hi:[1,0]
	v_add_u32_e32 v6, 0xa0, v4
	v_med3_f32 v5, v10, s47, v173
	v_med3_f32 v11, v11, s47, v173
	v_mov_b32_e32 v10, 0
	v_cvt_pk_fp8_f32 v10, v5, v11
	v_med3_f32 v5, v8, s47, v173
	v_med3_f32 v8, v9, s47, v173
	v_mov_b32_e32 v11, 0
	v_cvt_pk_fp8_f32 v10, v5, v8 op_sel:[0,0,1]
	v_med3_f32 v5, v14, s47, v173
	v_med3_f32 v8, v15, s47, v173
	v_cvt_pk_fp8_f32 v11, v5, v8
	v_med3_f32 v5, v12, s47, v173
	v_med3_f32 v8, v13, s47, v173
	v_cvt_pk_fp8_f32 v11, v5, v8 op_sel:[0,0,1]
	v_ashrrev_i32_e32 v7, 31, v6
	v_lshlrev_b64 v[6:7], 10, v[6:7]
	v_lshl_add_u64 v[6:7], s[12:13], 0, v[6:7]
	v_lshl_add_u64 v[6:7], v[6:7], 0, v[2:3]
	global_store_dwordx2 v[6:7], v[10:11], off
	v_pk_mul_f32 v[10:11], v[38:39], s[16:17] op_sel_hi:[1,0]
	v_pk_mul_f32 v[8:9], v[40:41], s[16:17] op_sel_hi:[1,0]
	v_med3_f32 v5, v10, s47, v173
	v_med3_f32 v11, v11, s47, v173
	v_mov_b32_e32 v10, 0
	v_cvt_pk_fp8_f32 v10, v5, v11
	v_pk_mul_f32 v[14:15], v[34:35], s[16:17] op_sel_hi:[1,0]
	v_med3_f32 v5, v8, s47, v173
	v_med3_f32 v8, v9, s47, v173
	v_cvt_pk_fp8_f32 v10, v5, v8 op_sel:[0,0,1]
	v_med3_f32 v5, v14, s47, v173
	v_med3_f32 v8, v15, s47, v173
	v_mov_b32_e32 v11, 0
	v_cvt_pk_fp8_f32 v11, v5, v8
	v_pk_mul_f32 v[12:13], v[36:37], s[16:17] op_sel_hi:[1,0]
	v_add_u32_e32 v4, 0xb0, v4
	v_med3_f32 v5, v12, s47, v173
	v_med3_f32 v8, v13, s47, v173
	v_cvt_pk_fp8_f32 v11, v5, v8 op_sel:[0,0,1]
	v_pk_mul_f32 v[8:9], v[28:29], s[16:17] op_sel_hi:[1,0]
	global_store_dwordx2 v[6:7], v[10:11], off offset:128
	v_pk_mul_f32 v[6:7], v[30:31], s[16:17] op_sel_hi:[1,0]
	v_pk_mul_f32 v[10:11], v[26:27], s[16:17] op_sel_hi:[1,0]
	v_ashrrev_i32_e32 v5, 31, v4
	v_med3_f32 v12, v6, s47, v173
	v_med3_f32 v7, v7, s47, v173
	v_mov_b32_e32 v6, 0
	v_lshlrev_b64 v[4:5], 10, v[4:5]
	v_cvt_pk_fp8_f32 v6, v12, v7
	v_lshl_add_u64 v[4:5], s[12:13], 0, v[4:5]
	v_lshl_add_u64 v[2:3], v[4:5], 0, v[2:3]
	v_pk_mul_f32 v[4:5], v[32:33], s[16:17] op_sel_hi:[1,0]
	v_mov_b32_e32 v7, 0
	v_med3_f32 v4, v4, s47, v173
	v_med3_f32 v5, v5, s47, v173
	v_cvt_pk_fp8_f32 v6, v4, v5 op_sel:[0,0,1]
	v_med3_f32 v4, v10, s47, v173
	v_med3_f32 v5, v11, s47, v173
	v_cvt_pk_fp8_f32 v7, v4, v5
	v_med3_f32 v4, v8, s47, v173
	v_med3_f32 v5, v9, s47, v173
	v_pk_mul_f32 v[10:11], v[18:19], s[16:17] op_sel_hi:[1,0]
	v_cvt_pk_fp8_f32 v7, v4, v5 op_sel:[0,0,1]
	v_pk_mul_f32 v[4:5], v[24:25], s[16:17] op_sel_hi:[1,0]
	v_pk_mul_f32 v[8:9], v[20:21], s[16:17] op_sel_hi:[1,0]
	v_med3_f32 v4, v4, s47, v173
	global_store_dwordx2 v[2:3], v[6:7], off
	v_pk_mul_f32 v[6:7], v[22:23], s[16:17] op_sel_hi:[1,0]
	v_med3_f32 v5, v5, s47, v173
	v_med3_f32 v12, v6, s47, v173
	v_med3_f32 v7, v7, s47, v173
	v_mov_b32_e32 v6, 0
	v_cvt_pk_fp8_f32 v6, v12, v7
	v_mov_b32_e32 v7, 0
	v_cvt_pk_fp8_f32 v6, v4, v5 op_sel:[0,0,1]
	v_med3_f32 v4, v10, s47, v173
	v_med3_f32 v5, v11, s47, v173
	v_cvt_pk_fp8_f32 v7, v4, v5
	v_med3_f32 v4, v8, s47, v173
	v_med3_f32 v5, v9, s47, v173
	v_cvt_pk_fp8_f32 v7, v4, v5 op_sel:[0,0,1]
	global_store_dwordx2 v[2:3], v[6:7], off offset:128
	s_cbranch_vccz .LBB0_1362
	s_waitcnt vmcnt(0)
	s_cmpk_gt_u32 s4, 0xff
	s_cbranch_scc1 .LBB0_1373
	s_barrier

.LBB0_1427:
	s_or_b64 exec, exec, s[8:9]
	s_waitcnt lgkmcnt(0)
	s_barrier
	s_load_dwordx4 s[4:7], s[84:85], 0xf8
	s_load_dwordx2 s[24:25], s[84:85], 0x108
	s_load_dwordx8 s[16:23], s[84:85], 0xd8
	v_mov_b32_e32 v39, v0
	s_waitcnt lgkmcnt(0)
	s_mov_b32 s0, s7
	v_and_b32_e32 v74, 63, v39
	s_mov_b32 s8, s25
	s_add_u32 s26, s24, 0x3e00000
	v_lshlrev_b32_e32 v34, 4, v74
	v_mov_b32_e32 v35, 0
	s_addc_u32 s27, s8, 0
	v_lshl_add_u64 v[2:3], s[22:23], 0, v[34:35]
	s_mov_b64 s[0:1], 0x3000
	v_lshl_add_u64 v[6:7], s[4:5], 0, v[34:35]
	v_lshl_add_u64 v[26:27], v[2:3], 0, s[0:1]
	v_lshl_add_u64 v[30:31], v[6:7], 0, s[0:1]
	s_movk_i32 s0, 0x3000
	s_add_u32 s22, s24, 0x3900000
	v_add_co_u32_e32 v2, vcc, s0, v2
	s_addc_u32 s23, s8, 0
	s_nop 0
	v_addc_co_u32_e32 v3, vcc, 0, v3, vcc
	s_add_u32 s14, s24, 0xa100000
	v_add_co_u32_e32 v6, vcc, s0, v6
	s_addc_u32 s15, s8, 0
	v_readlane_b32 s0, v253, 36
	v_readlane_b32 s1, v253, 37
	s_add_u32 s0, s14, s0
	s_addc_u32 s1, s15, s1
	v_readlane_b32 s4, v253, 38
	v_readlane_b32 s5, v253, 39
	s_add_u32 s4, s14, s4
	v_lshlrev_b32_e32 v34, 3, v74
	v_addc_co_u32_e32 v7, vcc, 0, v7, vcc
	s_addc_u32 s5, s15, s5
	v_lshl_add_u64 v[36:37], s[0:1], 0, v[34:35]
	global_load_dwordx4 v[2:5], v[2:3], off nt
	s_nop 0
	global_load_dwordx4 v[6:9], v[6:7], off nt
	s_nop 0
	global_load_dwordx4 v[10:13], v[26:27], off offset:1024
	global_load_dwordx4 v[14:17], v[26:27], off offset:2048
	global_load_dwordx4 v[18:21], v[30:31], off offset:1024
	global_load_dwordx4 v[22:25], v[30:31], off offset:2048
	s_nop 0
	global_load_dwordx4 v[26:29], v[26:27], off offset:3072
	s_nop 0
	global_load_dwordx4 v[30:33], v[30:31], off offset:3072
	v_lshl_add_u64 v[46:47], s[4:5], 0, v[34:35]
	global_load_dwordx2 v[64:65], v[36:37], off
	global_load_dwordx2 v[62:63], v[36:37], off offset:512
	global_load_dwordx2 v[60:61], v[36:37], off offset:1024
	global_load_dwordx2 v[58:59], v[36:37], off offset:1536
	global_load_dwordx2 v[44:45], v[46:47], off
	global_load_dwordx2 v[42:43], v[46:47], off offset:512
	global_load_dwordx2 v[40:41], v[46:47], off offset:1024
	s_nop 0
	global_load_dwordx2 v[36:37], v[46:47], off offset:1536
	s_mov_b32 s7, s8
	v_cmp_gt_u32_e64 s[12:13], 16, v74
	v_mov_b32_e32 v75, -1
	v_lshlrev_b32_e32 v38, 11, v74
	v_mov_b32_e32 v82, v35
	v_mov_b32_e32 v81, -1
	s_and_saveexec_b64 s[8:9], s[12:13]
	s_cbranch_execz .LBB0_1429
	v_readlane_b32 s0, v253, 34
	v_readlane_b32 s1, v253, 35
	s_mov_b32 s4, s0
	s_ashr_i32 s0, s0, 11
	s_ashr_i32 s1, s0, 31
	s_lshl_b64 s[0:1], s[0:1], 15
	s_and_b32 s4, s4, 0x7ff
	s_or_b32 s0, s0, s4
	s_ashr_i32 s4, s68, 11
	s_ashr_i32 s5, s4, 31
	s_lshl_b64 s[4:5], s[4:5], 15
	s_and_b32 s6, s68, 0x7ff
	s_or_b32 s4, s4, s6
	v_or_b32_e32 v46, s4, v38
	v_mov_b32_e32 v47, s5
	v_lshl_add_u64 v[48:49], v[46:47], 1, s[26:27]
	v_lshl_add_u64 v[46:47], v[46:47], 2, s[22:23]
	global_load_sshort v81, v[48:49], off
	global_load_dword v82, v[46:47], off
	v_or_b32_e32 v46, s0, v38
	v_mov_b32_e32 v47, s1
	v_lshl_add_u64 v[48:49], v[46:47], 1, s[26:27]
	v_lshl_add_u64 v[46:47], v[46:47], 2, s[22:23]
	global_load_sshort v75, v[48:49], off
	global_load_dword v35, v[46:47], off

.LBB0_1431:
	v_mov_b32_e32 v82, v71
	v_mov_b32_e32 v83, v68
	v_mov_b32_e32 v84, v70
	v_mov_b32_e32 v85, v69
	v_pk_add_f32 v[82:83], v[82:83], v[84:85]
	v_mov_b32_e32 v84, v67
	v_mov_b32_e32 v85, v62
	v_mov_b32_e32 v86, v66
	v_mov_b32_e32 v87, v63
	v_pk_add_f32 v[84:85], v[84:85], v[86:87]
	v_add_f32_e32 v34, v82, v83
	v_pk_add_f32 v[84:85], v[84:85], v[84:85] op_sel_hi:[0,1]
	v_add_f32_e32 v83, 0, v34
	v_add_f32_e32 v87, v64, v65
	v_add_f32_e32 v89, v60, v61
	v_mov_b32_e32 v86, v58
	v_mov_b32_e32 v88, v59
	v_mov_b32_e32 v84, v72
	v_mov_b32_e32 v82, v73
	v_pk_add_f32 v[86:87], v[86:87], v[88:89]
	v_pk_add_f32 v[82:83], v[84:85], v[82:83]
	s_ashr_i32 s35, s34, 31
	v_pk_add_f32 v[82:83], v[86:87], v[82:83]
	s_nop 0
	v_add_f32_e32 v34, v82, v83
	s_nop 1
	v_add_f32_dpp v34, v34, v34 quad_perm:[1,0,3,2] row_mask:0xf bank_mask:0xf bound_ctrl:1
	s_nop 1
	v_add_f32_dpp v34, v34, v34 quad_perm:[2,3,0,1] row_mask:0xf bank_mask:0xf bound_ctrl:1
	s_nop 1
	v_add_f32_dpp v34, v34, v34 row_half_mirror row_mask:0xf bank_mask:0xf bound_ctrl:1
	s_nop 1
	v_add_f32_dpp v34, v34, v34 row_mirror row_mask:0xf bank_mask:0xf bound_ctrl:1
	s_nop 0
	v_readlane_b32 s6, v34, 16
	v_readlane_b32 s8, v34, 48
	v_readlane_b32 s0, v34, 0
	v_readlane_b32 s1, v34, 32
	v_mov_b32_e32 v82, s6
	v_mov_b32_e32 v83, s8
	v_pk_add_f32 v[82:83], s[0:1], v[82:83]
	s_nop 0
	v_add_f32_e32 v46, v82, v83
	v_fmac_f32_e32 v71, 0xba800000, v46
	v_fmac_f32_e32 v70, 0xba800000, v46
	v_fmac_f32_e32 v69, 0xba800000, v46
	v_fmac_f32_e32 v68, 0xba800000, v46
	v_pk_mul_f32 v[82:83], v[68:69], v[68:69]
	v_pk_mul_f32 v[84:85], v[70:71], v[70:71]
	v_fmac_f32_e32 v67, 0xba800000, v46
	v_pk_mov_b32 v[86:87], v[84:85], v[82:83] op_sel:[1,0]
	v_mov_b32_e32 v85, v83
	v_fmac_f32_e32 v66, 0xba800000, v46
	v_fmac_f32_e32 v63, 0xba800000, v46
	v_fmac_f32_e32 v62, 0xba800000, v46
	v_pk_add_f32 v[82:83], v[86:87], v[84:85]
	v_pk_mul_f32 v[84:85], v[62:63], v[62:63]
	v_pk_mul_f32 v[86:87], v[66:67], v[66:67]
	v_fmac_f32_e32 v64, 0xba800000, v46
	v_pk_mov_b32 v[88:89], v[86:87], v[84:85] op_sel:[1,0]
	v_mov_b32_e32 v87, v85
	v_fmac_f32_e32 v65, 0xba800000, v46
	v_fmac_f32_e32 v60, 0xba800000, v46
	v_mul_f32_e32 v34, v64, v64
	v_pk_add_f32 v[84:85], v[88:89], v[86:87]
	v_fmac_f32_e32 v61, 0xba800000, v46
	v_pk_fma_f32 v[86:87], v[64:65], v[64:65], v[34:35] op_sel_hi:[1,1,0]
	v_mul_f32_e32 v34, v60, v60
	v_pk_add_f32 v[82:83], v[82:83], v[82:83] op_sel_hi:[0,1]
	v_pk_add_f32 v[84:85], v[84:85], v[84:85] op_sel_hi:[0,1]
	v_pk_fma_f32 v[88:89], v[60:61], v[60:61], v[34:35] op_sel_hi:[1,1,0]
	v_fmamk_f32 v73, v46, 0xba800000, v73
	v_fmamk_f32 v72, v46, 0xba800000, v72
	v_fmamk_f32 v59, v46, 0xba800000, v59
	v_fmac_f32_e32 v58, 0xba800000, v46
	v_mul_f32_e32 v86, v58, v58
	v_mul_f32_e32 v88, v59, v59
	v_mul_f32_e32 v82, v72, v72
	v_mul_f32_e32 v84, v73, v73
	v_pk_add_f32 v[86:87], v[86:87], v[88:89]
	v_pk_add_f32 v[82:83], v[82:83], v[84:85]
	s_nop 0
	v_pk_add_f32 v[82:83], v[86:87], v[82:83]
	s_nop 0
	v_add_f32_e32 v34, v82, v83
	s_nop 1
	v_add_f32_dpp v34, v34, v34 quad_perm:[1,0,3,2] row_mask:0xf bank_mask:0xf bound_ctrl:1
	s_nop 1
	v_add_f32_dpp v34, v34, v34 quad_perm:[2,3,0,1] row_mask:0xf bank_mask:0xf bound_ctrl:1
	s_nop 1
	v_add_f32_dpp v34, v34, v34 row_half_mirror row_mask:0xf bank_mask:0xf bound_ctrl:1
	s_nop 1
	v_add_f32_dpp v34, v34, v34 row_mirror row_mask:0xf bank_mask:0xf bound_ctrl:1
	s_nop 0
	v_readlane_b32 s6, v34, 16
	v_readlane_b32 s8, v34, 48
	v_readlane_b32 s0, v34, 0
	v_readlane_b32 s1, v34, 32
	v_mov_b32_e32 v82, s6
	v_mov_b32_e32 v83, s8
	v_pk_add_f32 v[82:83], s[0:1], v[82:83]
	s_mov_b32 s0, 0xf800000
	v_add_f32_e32 v34, v82, v83
	v_fmamk_f32 v34, v34, 0x3a800000, v76
	v_mul_f32_e32 v46, 0x4f800000, v34
	v_cmp_gt_f32_e32 vcc, s0, v34
	s_nop 1
	v_cndmask_b32_e32 v34, v34, v46, vcc
	v_sqrt_f32_e32 v46, v34
	s_nop 0
	v_add_u32_e32 v81, -1, v46
	v_fma_f32 v82, -v81, v46, v34
	v_cmp_ge_f32_e64 s[14:15], 0, v82
	v_add_u32_e32 v82, 1, v46
	s_nop 0
	v_cndmask_b32_e64 v81, v46, v81, s[14:15]
	v_fma_f32 v46, -v82, v46, v34
	v_cmp_lt_f32_e64 s[14:15], 0, v46
	s_nop 1
	v_cndmask_b32_e64 v46, v81, v82, s[14:15]
	v_mul_f32_e32 v81, 0x37800000, v46
	v_cndmask_b32_e32 v46, v46, v81, vcc
	v_cmp_class_f32_e32 vcc, v34, v77
	s_nop 1
	v_cndmask_b32_e32 v34, v46, v34, vcc
	v_div_scale_f32 v46, s[0:1], v34, v34, 1.0
	v_rcp_f32_e32 v81, v46
	s_lshl_b64 s[0:1], s[34:35], 11
	s_sub_i32 s34, s30, s33
	s_cmp_gt_i32 s34, 0xffff
	v_fma_f32 v82, -v46, v81, 1.0
	v_fmac_f32_e32 v81, v82, v81
	v_div_scale_f32 v82, vcc, 1.0, v34, 1.0
	v_mul_f32_e32 v83, v82, v81
	v_fma_f32 v84, -v46, v83, v82
	v_fmac_f32_e32 v83, v84, v81
	v_fma_f32 v46, -v46, v83, v82
	v_div_fmas_f32 v46, v46, v81, v83
	v_div_fixup_f32 v34, v46, v34, 1.0
	v_pk_mul_f32 v[66:67], v[66:67], v[34:35] op_sel_hi:[1,0]
	v_pk_mul_f32 v[62:63], v[62:63], v[34:35] op_sel_hi:[1,0]
	v_pk_fma_f32 v[66:67], v[10:11], v[66:67], v[18:19]
	v_pk_fma_f32 v[62:63], v[12:13], v[62:63], v[20:21]
	v_cvt_pk_bf16_f32 v66, v66, v67
	v_cvt_pk_bf16_f32 v67, v62, v63
	v_pk_mul_f32 v[62:63], v[64:65], v[34:35] op_sel_hi:[1,0]
	v_pk_mul_f32 v[60:61], v[60:61], v[34:35] op_sel_hi:[1,0]
	v_pk_fma_f32 v[62:63], v[14:15], v[62:63], v[22:23]
	v_pk_fma_f32 v[60:61], v[16:17], v[60:61], v[24:25]
	v_pk_mul_f32 v[70:71], v[70:71], v[34:35] op_sel_hi:[1,0]
	v_pk_mul_f32 v[68:69], v[68:69], v[34:35] op_sel_hi:[1,0]
	v_cvt_pk_bf16_f32 v62, v62, v63
	v_cvt_pk_bf16_f32 v63, v60, v61
	v_pk_mul_f32 v[58:59], v[58:59], v[34:35] op_sel_hi:[1,0]
	v_pk_mul_f32 v[60:61], v[72:73], v[34:35] op_sel_hi:[1,0]
	v_pk_fma_f32 v[68:69], v[4:5], v[68:69], v[8:9]
	v_pk_fma_f32 v[70:71], v[2:3], v[70:71], v[6:7]
	v_pk_fma_f32 v[60:61], v[28:29], v[60:61], v[32:33]
	v_pk_fma_f32 v[58:59], v[26:27], v[58:59], v[30:31]
	v_cvt_pk_bf16_f32 v70, v70, v71
	v_cvt_pk_bf16_f32 v71, v68, v69
	v_lshl_add_u64 v[68:69], v[48:49], 0, s[0:1]
	v_cvt_pk_bf16_f32 v58, v58, v59
	v_cvt_pk_bf16_f32 v59, v60, v61
	global_store_dwordx2 v[68:69], v[62:63], off offset:1024
	global_store_dwordx2 v[68:69], v[58:59], off offset:1536
	v_mov_b32_e32 v64, v44
	v_mov_b32_e32 v65, v45
	v_mov_b32_e32 v62, v42
	v_mov_b32_e32 v63, v43
	v_mov_b32_e32 v60, v40
	v_mov_b32_e32 v61, v41
	v_mov_b32_e32 v58, v36
	v_mov_b32_e32 v59, v37
	s_waitcnt vmcnt(0) lgkmcnt(0)
	v_mov_b64_e32 v[36:37], v[50:51]
	v_mov_b64_e32 v[40:41], v[52:53]
	v_mov_b64_e32 v[42:43], v[54:55]
	v_mov_b64_e32 v[44:45], v[56:57]
	v_mov_b32_e32 v81, v75
	v_mov_b32_e32 v75, v79
	v_mov_b32_e32 v82, v35
	v_mov_b32_e32 v35, v80
	global_store_dwordx2 v[68:69], v[70:71], off
	global_store_dwordx2 v[68:69], v[66:67], off offset:512
	s_cbranch_scc1 .LBB0_1441
.LBB0_1432:
	s_add_i32 s30, s34, s94
	s_cmp_gt_i32 s30, 0xffff
	v_mov_b32_e32 v80, v35
	s_cbranch_scc1 .LBB0_1436
	s_ashr_i32 s31, s30, 31
	s_lshl_b64 s[0:1], s[30:31], 11
	v_lshl_add_u64 v[50:51], v[48:49], 0, s[0:1]
	global_load_dwordx2 v[56:57], v[50:51], off
	global_load_dwordx2 v[54:55], v[50:51], off offset:512
	global_load_dwordx2 v[52:53], v[50:51], off offset:1024
	s_nop 0
	global_load_dwordx2 v[50:51], v[50:51], off offset:1536
	v_mov_b32_e32 v79, v75
	v_mov_b32_e32 v80, v35
	s_and_saveexec_b64 s[14:15], s[12:13]
	s_cbranch_execz .LBB0_1435
	s_ashr_i32 s0, s30, 11
	s_ashr_i32 s1, s0, 31
	s_lshl_b64 s[0:1], s[0:1], 15
	v_or_b32_e32 v34, s0, v38
	s_and_b32 s0, s30, 0x7ff
	v_mov_b32_e32 v67, s1
	v_or_b32_e32 v66, s0, v34
	v_lshl_add_u64 v[68:69], v[66:67], 1, s[26:27]
	v_lshl_add_u64 v[66:67], v[66:67], 2, s[22:23]
	global_load_sshort v79, v[68:69], off
	global_load_dword v80, v[66:67], off

.LBB0_1438:
	s_add_u32 s10, s38, -1
	s_addc_u32 s11, s39, -1
	s_lshl_b32 s8, s8, 5
	s_add_i32 s8, s8, s6
	s_ashr_i32 s9, s8, 31
	s_ashr_i32 s37, s36, 31
	s_and_b64 vcc, s[10:11], s[38:39]
	s_lshl_b64 s[8:9], s[8:9], 18
	s_lshl_b64 s[10:11], s[36:37], 10
	s_add_u32 s8, s4, s8
	s_addc_u32 s9, s5, s9
	s_add_u32 s8, s8, s10
	s_addc_u32 s9, s9, s11
	s_lshl_b32 s1, s1, 5
	s_add_i32 s10, s1, s6
	s_ashr_i32 s11, s10, 31
	s_ashr_i32 s15, s14, 31
	v_lshlrev_b32_e32 v46, 2, v74
	s_lshl_b64 s[10:11], s[10:11], 18
	s_lshl_b64 s[14:15], s[14:15], 10
	v_lshl_add_u64 v[84:85], s[8:9], 0, v[46:47]
	s_add_u32 s1, s4, s10
	global_load_dword v83, v[84:85], off
	s_addc_u32 s11, s5, s11
	s_add_u32 s10, s1, s14
	s_addc_u32 s11, s11, s15
	v_lshl_add_u64 v[86:87], s[10:11], 0, v[46:47]
	global_load_dword v90, v[86:87], off
	global_load_dword v92, v[84:85], off offset:256
	global_load_dword v93, v[86:87], off offset:256
	global_load_dword v94, v[84:85], off offset:512
	global_load_dword v95, v[86:87], off offset:512
	global_load_dword v96, v[84:85], off offset:768
	global_load_dword v97, v[86:87], off offset:768
	v_mul_f32_e32 v46, s0, v78
	s_cmp_eq_u64 vcc, 0
	s_waitcnt vmcnt(0) lgkmcnt(0)
	v_cvt_pk_f32_fp8_e32 v[88:89], v90
	v_cvt_pk_f32_fp8_sdwa v[90:91], v90 src0_sel:WORD_1
	v_cvt_pk_f32_fp8_e32 v[84:85], v83
	v_cvt_pk_f32_fp8_sdwa v[86:87], v83 src0_sel:WORD_1
	v_pk_mul_f32 v[88:89], v[34:35], v[88:89] op_sel_hi:[0,1]
	v_pk_mul_f32 v[90:91], v[34:35], v[90:91] op_sel_hi:[0,1]
	v_pk_fma_f32 v[84:85], v[46:47], v[84:85], v[88:89] op_sel_hi:[0,1,1]
	v_pk_fma_f32 v[86:87], v[46:47], v[86:87], v[90:91] op_sel_hi:[0,1,1]
	v_cvt_pk_f32_fp8_e32 v[88:89], v93
	v_cvt_pk_f32_fp8_sdwa v[90:91], v93 src0_sel:WORD_1
	v_pk_add_f32 v[68:69], v[68:69], v[86:87]
	v_pk_add_f32 v[70:71], v[70:71], v[84:85]
	v_cvt_pk_f32_fp8_e32 v[84:85], v92
	v_cvt_pk_f32_fp8_sdwa v[86:87], v92 src0_sel:WORD_1
	v_pk_mul_f32 v[90:91], v[34:35], v[90:91] op_sel_hi:[0,1]
	v_pk_mul_f32 v[88:89], v[34:35], v[88:89] op_sel_hi:[0,1]
	v_pk_fma_f32 v[84:85], v[46:47], v[84:85], v[88:89] op_sel_hi:[0,1,1]
	v_pk_fma_f32 v[86:87], v[46:47], v[86:87], v[90:91] op_sel_hi:[0,1,1]
	v_cvt_pk_f32_fp8_e32 v[88:89], v95
	v_cvt_pk_f32_fp8_sdwa v[90:91], v95 src0_sel:WORD_1
	v_pk_add_f32 v[62:63], v[62:63], v[86:87]
	v_pk_add_f32 v[66:67], v[66:67], v[84:85]
	v_cvt_pk_f32_fp8_e32 v[84:85], v94
	v_cvt_pk_f32_fp8_sdwa v[86:87], v94 src0_sel:WORD_1
	v_pk_mul_f32 v[90:91], v[34:35], v[90:91] op_sel_hi:[0,1]
	v_pk_mul_f32 v[88:89], v[34:35], v[88:89] op_sel_hi:[0,1]
	v_pk_fma_f32 v[84:85], v[46:47], v[84:85], v[88:89] op_sel_hi:[0,1,1]
	v_pk_fma_f32 v[86:87], v[46:47], v[86:87], v[90:91] op_sel_hi:[0,1,1]
	v_cvt_pk_f32_fp8_e32 v[88:89], v97
	v_cvt_pk_f32_fp8_sdwa v[90:91], v97 src0_sel:WORD_1
	v_pk_add_f32 v[60:61], v[60:61], v[86:87]
	v_pk_add_f32 v[64:65], v[64:65], v[84:85]
	v_cvt_pk_f32_fp8_e32 v[84:85], v96
	v_cvt_pk_f32_fp8_sdwa v[86:87], v96 src0_sel:WORD_1
	v_pk_mul_f32 v[90:91], v[34:35], v[90:91] op_sel_hi:[0,1]
	v_pk_mul_f32 v[88:89], v[34:35], v[88:89] op_sel_hi:[0,1]
	v_pk_fma_f32 v[84:85], v[46:47], v[84:85], v[88:89] op_sel_hi:[0,1,1]
	v_pk_fma_f32 v[86:87], v[46:47], v[86:87], v[90:91] op_sel_hi:[0,1,1]
	v_pk_add_f32 v[72:73], v[72:73], v[86:87]
	v_pk_add_f32 v[58:59], v[58:59], v[84:85]
	s_cbranch_scc1 .LBB0_1431

.LBB0_1444:
	s_mul_hi_i32 s0, s11, 0x2aaaaaab
	s_lshr_b32 s1, s0, 31
	s_ashr_i32 s0, s0, 8
	s_add_i32 s14, s0, s1
	s_mul_i32 s0, s14, 0xfffffa00
	s_add_i32 s24, s11, s0
	s_lshr_b32 s0, s24, 22
	s_and_b32 s0, s0, 0x1ff
	s_add_i32 s25, s24, s0
	s_and_b32 s0, s25, 0xfe00
	s_sub_i32 s0, s24, s0
	s_sext_i32_i16 s1, s0
	s_bfe_u32 s1, s1, 0x5001a
	s_add_i32 s1, s0, s1
	s_sext_i32_i16 s12, s1
	s_and_b32 s1, s1, 0xffe0
	s_lshl_b32 s23, s12, 1
	s_sub_i32 s0, s0, s1
	s_andn2_b32 s23, s23, 63
	s_sext_i32_i16 s22, s0
	s_lshl_b32 s12, s22, 5
	v_or_b32_e32 v20, s23, v26
	s_mov_b64 s[20:21], -1
	s_cmpk_gt_i32 s24, 0x3ff
	v_ashrrev_i32_e32 v21, 31, v20
	v_or_b32_e32 v18, 8, v20
	v_or_b32_e32 v16, 16, v20
	v_or_b32_e32 v14, 24, v20
	v_or_b32_e32 v12, 32, v20
	v_or_b32_e32 v10, 40, v20
	v_or_b32_e32 v8, 48, v20
	v_or_b32_e32 v6, 56, v20
	s_cbranch_scc0 .LBB0_1446
	s_ashr_i32 s15, s14, 31
	s_lshl_b64 s[0:1], s[14:15], 20
	s_lshl_b64 s[20:21], s[14:15], 22
	s_add_u32 s15, s8, s20
	s_addc_u32 s20, s9, s21
	s_add_u32 s21, s6, s0
	s_addc_u32 s26, s7, s1
	s_ashr_i32 s13, s12, 31
	s_lshl_b64 s[0:1], s[12:13], 2
	s_add_u32 s0, s15, s0
	s_addc_u32 s1, s20, s1
	v_lshl_add_u64 v[72:73], s[0:1], 0, v[2:3]
	v_lshlrev_b64 v[22:23], 12, v[20:21]
	v_lshl_add_u64 v[22:23], v[72:73], 0, v[22:23]
	v_ashrrev_i32_e32 v19, 31, v18
	global_load_dwordx4 v[22:25], v[22:23], off nt
	v_lshlrev_b64 v[48:49], 12, v[18:19]
	v_lshl_add_u64 v[48:49], v[72:73], 0, v[48:49]
	v_ashrrev_i32_e32 v17, 31, v16
	global_load_dwordx4 v[48:51], v[48:49], off nt
	v_lshlrev_b64 v[52:53], 12, v[16:17]
	v_lshl_add_u64 v[52:53], v[72:73], 0, v[52:53]
	v_ashrrev_i32_e32 v15, 31, v14
	global_load_dwordx4 v[52:55], v[52:53], off nt
	v_lshlrev_b64 v[56:57], 12, v[14:15]
	v_lshl_add_u64 v[56:57], v[72:73], 0, v[56:57]
	v_ashrrev_i32_e32 v13, 31, v12
	global_load_dwordx4 v[56:59], v[56:57], off nt
	v_lshlrev_b64 v[60:61], 12, v[12:13]
	v_lshl_add_u64 v[60:61], v[72:73], 0, v[60:61]
	v_ashrrev_i32_e32 v11, 31, v10
	global_load_dwordx4 v[60:63], v[60:61], off nt
	v_lshlrev_b64 v[64:65], 12, v[10:11]
	v_lshl_add_u64 v[64:65], v[72:73], 0, v[64:65]
	v_ashrrev_i32_e32 v9, 31, v8
	global_load_dwordx4 v[64:67], v[64:65], off nt
	v_lshlrev_b64 v[68:69], 12, v[8:9]
	v_lshl_add_u64 v[68:69], v[72:73], 0, v[68:69]
	v_ashrrev_i32_e32 v7, 31, v6
	global_load_dwordx4 v[68:71], v[68:69], off nt
	v_lshlrev_b64 v[74:75], 12, v[6:7]
	v_lshl_add_u64 v[72:73], v[72:73], 0, v[74:75]
	global_load_dwordx4 v[72:75], v[72:73], off nt
	s_ashr_i32 s1, s23, 31
	s_add_u32 s0, s21, s23
	s_addc_u32 s1, s26, s1
	s_waitcnt vmcnt(0)
	ds_write2_b32 v31, v22, v23 offset1:1
	ds_write2_b32 v31, v24, v25 offset0:2 offset1:3
	s_waitcnt vmcnt(6)
	ds_write2_b32 v32, v48, v49 offset1:1
	ds_write2_b32 v33, v50, v51 offset1:1
	s_waitcnt vmcnt(5)
	ds_write2_b32 v34, v52, v53 offset1:1
	ds_write2_b32 v35, v54, v55 offset1:1
	s_waitcnt vmcnt(4)
	ds_write2_b32 v36, v56, v57 offset1:1
	ds_write2_b32 v37, v58, v59 offset1:1
	s_waitcnt vmcnt(3)
	ds_write2_b32 v38, v60, v61 offset1:1
	ds_write2_b32 v39, v62, v63 offset1:1
	s_waitcnt vmcnt(2)
	ds_write2_b32 v40, v64, v65 offset1:1
	ds_write2_b32 v41, v66, v67 offset1:1
	s_waitcnt vmcnt(1)
	ds_write2_b32 v42, v68, v69 offset1:1
	ds_write2_b32 v43, v70, v71 offset1:1
	s_waitcnt vmcnt(0)
	ds_write2_b32 v44, v72, v73 offset1:1
	ds_write2_b32 v45, v74, v75 offset1:1
	s_waitcnt lgkmcnt(0)
	ds_read_b32 v7, v30
	ds_read_b32 v9, v30 offset:132
	ds_read_b32 v11, v30 offset:264
	ds_read_b32 v13, v30 offset:396
	v_mov_b32_e32 v24, v3
	s_waitcnt lgkmcnt(0)
	v_mul_f32_e32 v7, 0x43000000, v7
	s_waitcnt lgkmcnt(2)
	v_mul_f32_e32 v9, 0x43000000, v9
	v_med3_f32 v7, v7, s10, v46
	v_med3_f32 v9, v9, s10, v46
	v_cvt_pk_fp8_f32 v24, v7, v9
	s_waitcnt lgkmcnt(1)
	v_mul_f32_e32 v11, 0x43000000, v11
	s_waitcnt lgkmcnt(0)
	v_mul_f32_e32 v13, 0x43000000, v13
	v_med3_f32 v7, v11, s10, v46
	v_med3_f32 v9, v13, s10, v46
	v_cvt_pk_fp8_f32 v24, v7, v9 op_sel:[0,0,1]
	ds_read_b32 v7, v30 offset:528
	ds_read_b32 v9, v30 offset:660
	ds_read_b32 v11, v30 offset:792
	ds_read_b32 v13, v30 offset:924
	v_mov_b32_e32 v25, v3
	s_waitcnt lgkmcnt(3)
	v_mul_f32_e32 v7, 0x43000000, v7
	s_waitcnt lgkmcnt(2)
	v_mul_f32_e32 v9, 0x43000000, v9
	v_med3_f32 v7, v7, s10, v46
	v_med3_f32 v9, v9, s10, v46
	v_cvt_pk_fp8_f32 v25, v7, v9
	s_waitcnt lgkmcnt(1)
	v_mul_f32_e32 v11, 0x43000000, v11
	s_waitcnt lgkmcnt(0)
	v_mul_f32_e32 v13, 0x43000000, v13
	v_med3_f32 v7, v11, s10, v46
	v_med3_f32 v9, v13, s10, v46
	v_cvt_pk_fp8_f32 v25, v7, v9 op_sel:[0,0,1]
	v_or_b32_e32 v48, s12, v26
	v_ashrrev_i32_e32 v49, 31, v48
	v_lshl_add_u64 v[22:23], s[0:1], 0, v[4:5]
	v_lshlrev_b64 v[48:49], 10, v[48:49]
	v_lshl_add_u64 v[48:49], v[22:23], 0, v[48:49]
	global_store_dwordx2 v[48:49], v[24:25], off
	ds_read_b32 v7, v30 offset:32
	ds_read_b32 v9, v30 offset:164
	ds_read_b32 v11, v30 offset:296
	ds_read_b32 v13, v30 offset:428
	v_mov_b32_e32 v24, v3
	s_waitcnt lgkmcnt(0)
	v_mul_f32_e32 v7, 0x43000000, v7
	v_mul_f32_e32 v9, 0x43000000, v9
	v_med3_f32 v7, v7, s10, v46
	v_med3_f32 v9, v9, s10, v46
	v_cvt_pk_fp8_f32 v24, v7, v9
	v_mul_f32_e32 v11, 0x43000000, v11
	v_mul_f32_e32 v13, 0x43000000, v13
	v_med3_f32 v7, v11, s10, v46
	v_med3_f32 v9, v13, s10, v46
	v_cvt_pk_fp8_f32 v24, v7, v9 op_sel:[0,0,1]
	ds_read_b32 v7, v30 offset:560
	ds_read_b32 v9, v30 offset:692
	ds_read_b32 v11, v30 offset:824
	ds_read_b32 v13, v30 offset:956
	v_mov_b32_e32 v25, v3
	s_waitcnt lgkmcnt(0)
	v_mul_f32_e32 v7, 0x43000000, v7
	v_mul_f32_e32 v9, 0x43000000, v9
	v_med3_f32 v7, v7, s10, v46
	v_med3_f32 v9, v9, s10, v46
	v_cvt_pk_fp8_f32 v25, v7, v9
	v_mul_f32_e32 v11, 0x43000000, v11
	v_mul_f32_e32 v13, 0x43000000, v13
	v_med3_f32 v7, v11, s10, v46
	v_med3_f32 v9, v13, s10, v46
	v_cvt_pk_fp8_f32 v25, v7, v9 op_sel:[0,0,1]
	v_or_b32_e32 v48, s12, v27
	v_ashrrev_i32_e32 v49, 31, v48
	v_lshlrev_b64 v[48:49], 10, v[48:49]
	v_lshl_add_u64 v[48:49], v[22:23], 0, v[48:49]
	global_store_dwordx2 v[48:49], v[24:25], off
	ds_read_b32 v7, v30 offset:64
	ds_read_b32 v9, v30 offset:196
	ds_read_b32 v11, v30 offset:328
	ds_read_b32 v13, v30 offset:460
	v_mov_b32_e32 v24, v3
	s_waitcnt lgkmcnt(0)
	v_mul_f32_e32 v7, 0x43000000, v7
	v_mul_f32_e32 v9, 0x43000000, v9
	v_med3_f32 v7, v7, s10, v46
	v_med3_f32 v9, v9, s10, v46
	v_cvt_pk_fp8_f32 v24, v7, v9
	v_mul_f32_e32 v11, 0x43000000, v11
	v_mul_f32_e32 v13, 0x43000000, v13
	v_med3_f32 v7, v11, s10, v46
	v_med3_f32 v9, v13, s10, v46
	v_cvt_pk_fp8_f32 v24, v7, v9 op_sel:[0,0,1]
	ds_read_b32 v7, v30 offset:592
	ds_read_b32 v9, v30 offset:724
	ds_read_b32 v11, v30 offset:856
	ds_read_b32 v13, v30 offset:988
	v_mov_b32_e32 v25, v3
	s_waitcnt lgkmcnt(0)
	v_mul_f32_e32 v7, 0x43000000, v7
	v_mul_f32_e32 v9, 0x43000000, v9
	v_med3_f32 v7, v7, s10, v46
	v_med3_f32 v9, v9, s10, v46
	v_cvt_pk_fp8_f32 v25, v7, v9
	v_mul_f32_e32 v11, 0x43000000, v11
	v_mul_f32_e32 v13, 0x43000000, v13
	v_med3_f32 v7, v11, s10, v46
	v_med3_f32 v9, v13, s10, v46
	v_cvt_pk_fp8_f32 v25, v7, v9 op_sel:[0,0,1]
	v_or_b32_e32 v48, s12, v28
	v_ashrrev_i32_e32 v49, 31, v48
	v_lshlrev_b64 v[48:49], 10, v[48:49]
	v_lshl_add_u64 v[48:49], v[22:23], 0, v[48:49]
	global_store_dwordx2 v[48:49], v[24:25], off
	ds_read_b32 v7, v30 offset:96
	ds_read_b32 v9, v30 offset:228
	ds_read_b32 v11, v30 offset:360
	ds_read_b32 v13, v30 offset:492
	v_mov_b32_e32 v24, v3
	s_waitcnt lgkmcnt(0)
	v_mul_f32_e32 v7, 0x43000000, v7
	v_mul_f32_e32 v9, 0x43000000, v9
	v_med3_f32 v7, v7, s10, v46
	v_med3_f32 v9, v9, s10, v46
	v_cvt_pk_fp8_f32 v24, v7, v9
	v_mul_f32_e32 v11, 0x43000000, v11
	v_mul_f32_e32 v13, 0x43000000, v13
	v_med3_f32 v7, v11, s10, v46
	v_med3_f32 v9, v13, s10, v46
	v_cvt_pk_fp8_f32 v24, v7, v9 op_sel:[0,0,1]
	ds_read_b32 v7, v30 offset:624
	ds_read_b32 v9, v30 offset:756
	ds_read_b32 v11, v30 offset:888
	ds_read_b32 v13, v30 offset:1020
	v_mov_b32_e32 v25, v3
	s_waitcnt lgkmcnt(0)
	v_mul_f32_e32 v7, 0x43000000, v7
	v_mul_f32_e32 v9, 0x43000000, v9
	v_med3_f32 v7, v7, s10, v46
	v_med3_f32 v9, v9, s10, v46
	v_cvt_pk_fp8_f32 v25, v7, v9
	v_mul_f32_e32 v11, 0x43000000, v11
	v_mul_f32_e32 v13, 0x43000000, v13
	v_med3_f32 v7, v11, s10, v46
	v_med3_f32 v9, v13, s10, v46
	v_cvt_pk_fp8_f32 v25, v7, v9 op_sel:[0,0,1]
	v_or_b32_e32 v48, s12, v29
	v_ashrrev_i32_e32 v49, 31, v48
	v_lshlrev_b64 v[48:49], 10, v[48:49]
	v_lshl_add_u64 v[22:23], v[22:23], 0, v[48:49]
	global_store_dwordx2 v[22:23], v[24:25], off
	s_waitcnt lgkmcnt(0)
	s_cbranch_execnz .LBB0_1443
	s_branch .LBB0_1447

.LBB0_1447:
	s_sext_i32_i16 s0, s25
	s_lshr_b32 s0, s0, 9
	s_addk_i32 s24, 0x1ff
	s_cmpk_lt_u32 s24, 0x3ff
	s_cselect_b32 s13, s17, s19
	s_cselect_b32 s21, s16, s18
	s_ashr_i32 s15, s14, 31
	s_sext_i32_i16 s20, s0
	s_lshl_b64 s[0:1], s[14:15], 22
	s_add_u32 s21, s21, s0
	s_addc_u32 s24, s13, s1
	s_lshl_b64 s[0:1], s[14:15], 21
	s_add_u32 s14, s4, s0
	s_addc_u32 s15, s5, s1
	s_ashr_i32 s13, s12, 31
	s_lshl_b64 s[0:1], s[12:13], 2
	s_add_u32 s0, s21, s0
	s_addc_u32 s1, s24, s1
	v_lshl_add_u64 v[22:23], s[0:1], 0, v[2:3]
	s_mov_b64 s[0:1], 0x8000000
	v_lshl_add_u64 v[24:25], v[22:23], 0, s[0:1]
	v_lshlrev_b64 v[20:21], 12, v[20:21]
	v_lshl_add_u64 v[20:21], v[24:25], 0, v[20:21]
	v_ashrrev_i32_e32 v19, 31, v18
	global_load_dwordx4 v[20:23], v[20:21], off nt
	v_lshlrev_b64 v[18:19], 12, v[18:19]
	v_lshl_add_u64 v[18:19], v[24:25], 0, v[18:19]
	v_ashrrev_i32_e32 v17, 31, v16
	global_load_dwordx4 v[48:51], v[18:19], off nt
	v_lshlrev_b64 v[16:17], 12, v[16:17]
	v_lshl_add_u64 v[16:17], v[24:25], 0, v[16:17]
	v_ashrrev_i32_e32 v15, 31, v14
	global_load_dwordx4 v[16:19], v[16:17], off nt
	v_lshlrev_b64 v[14:15], 12, v[14:15]
	v_lshl_add_u64 v[14:15], v[24:25], 0, v[14:15]
	v_ashrrev_i32_e32 v13, 31, v12
	global_load_dwordx4 v[52:55], v[14:15], off nt
	v_lshlrev_b64 v[12:13], 12, v[12:13]
	v_lshl_add_u64 v[12:13], v[24:25], 0, v[12:13]
	v_ashrrev_i32_e32 v11, 31, v10
	global_load_dwordx4 v[12:15], v[12:13], off nt
	v_lshlrev_b64 v[10:11], 12, v[10:11]
	v_lshl_add_u64 v[10:11], v[24:25], 0, v[10:11]
	v_ashrrev_i32_e32 v9, 31, v8
	global_load_dwordx4 v[56:59], v[10:11], off nt
	v_lshlrev_b64 v[8:9], 12, v[8:9]
	v_lshl_add_u64 v[8:9], v[24:25], 0, v[8:9]
	v_ashrrev_i32_e32 v7, 31, v6
	global_load_dwordx4 v[8:11], v[8:9], off nt
	v_lshlrev_b64 v[6:7], 12, v[6:7]
	v_lshl_add_u64 v[6:7], v[24:25], 0, v[6:7]
	global_load_dwordx4 v[60:63], v[6:7], off nt
	s_lshl_b32 s1, s20, 7
	s_ashr_i32 s0, s23, 31
	s_add_u32 s14, s14, s23
	s_addc_u32 s15, s15, s0
	s_lshl_b32 s0, s22, 6
	s_and_b32 s0, s0, 0xffffff00
	s_add_i32 s0, s0, s1
	s_and_b32 s1, s12, 0x60
	s_or_b32 s12, s0, s1
	v_lshl_add_u64 v[6:7], s[14:15], 0, v[4:5]
	s_waitcnt vmcnt(0)
	ds_write2_b32 v31, v20, v21 offset1:1
	ds_write2_b32 v31, v22, v23 offset0:2 offset1:3
	ds_write2_b32 v32, v48, v49 offset1:1
	ds_write2_b32 v33, v50, v51 offset1:1
	ds_write2_b32 v34, v16, v17 offset1:1
	ds_write2_b32 v35, v18, v19 offset1:1
	ds_write2_b32 v36, v52, v53 offset1:1
	ds_write2_b32 v37, v54, v55 offset1:1
	ds_write2_b32 v38, v12, v13 offset1:1
	ds_write2_b32 v39, v14, v15 offset1:1
	ds_write2_b32 v40, v56, v57 offset1:1
	ds_write2_b32 v41, v58, v59 offset1:1
	ds_write2_b32 v42, v8, v9 offset1:1
	ds_write2_b32 v43, v10, v11 offset1:1
	ds_write2_b32 v44, v60, v61 offset1:1
	ds_write2_b32 v45, v62, v63 offset1:1
	s_waitcnt lgkmcnt(0)
	ds_read_b32 v8, v30
	ds_read_b32 v9, v30 offset:132
	ds_read_b32 v10, v30 offset:264
	ds_read_b32 v11, v30 offset:396
	s_waitcnt lgkmcnt(0)
	v_mul_f32_e32 v8, 0x42800000, v8
	v_mul_f32_e32 v9, 0x42800000, v9
	v_med3_f32 v12, v8, s10, v46
	v_med3_f32 v9, v9, s10, v46
	v_mov_b32_e32 v8, v3
	v_cvt_pk_fp8_f32 v8, v12, v9
	v_mul_f32_e32 v10, 0x42800000, v10
	v_mul_f32_e32 v11, 0x42800000, v11
	v_med3_f32 v9, v10, s10, v46
	v_med3_f32 v10, v11, s10, v46
	v_cvt_pk_fp8_f32 v8, v9, v10 op_sel:[0,0,1]
	ds_read_b32 v9, v30 offset:528
	ds_read_b32 v10, v30 offset:660
	ds_read_b32 v11, v30 offset:792
	ds_read_b32 v12, v30 offset:924
	s_waitcnt lgkmcnt(3)
	v_mul_f32_e32 v9, 0x42800000, v9
	s_waitcnt lgkmcnt(2)
	v_mul_f32_e32 v10, 0x42800000, v10
	v_med3_f32 v13, v9, s10, v46
	v_med3_f32 v10, v10, s10, v46
	v_mov_b32_e32 v9, v3
	v_cvt_pk_fp8_f32 v9, v13, v10
	s_waitcnt lgkmcnt(1)
	v_mul_f32_e32 v11, 0x42800000, v11
	s_waitcnt lgkmcnt(0)
	v_mul_f32_e32 v12, 0x42800000, v12
	v_med3_f32 v10, v11, s10, v46
	v_med3_f32 v11, v12, s10, v46
	v_cvt_pk_fp8_f32 v9, v10, v11 op_sel:[0,0,1]
	v_or_b32_e32 v10, s12, v26
	v_ashrrev_i32_e32 v11, 31, v10
	v_lshlrev_b64 v[10:11], 10, v[10:11]
	v_lshl_add_u64 v[10:11], v[6:7], 0, v[10:11]
	global_store_dwordx2 v[10:11], v[8:9], off
	ds_read_b32 v8, v30 offset:32
	ds_read_b32 v9, v30 offset:164
	ds_read_b32 v10, v30 offset:296
	ds_read_b32 v11, v30 offset:428
	s_waitcnt lgkmcnt(0)
	v_mul_f32_e32 v8, 0x42800000, v8
	v_mul_f32_e32 v9, 0x42800000, v9
	v_med3_f32 v12, v8, s10, v46
	v_med3_f32 v9, v9, s10, v46
	v_mov_b32_e32 v8, v3
	v_cvt_pk_fp8_f32 v8, v12, v9
	v_mul_f32_e32 v10, 0x42800000, v10
	v_mul_f32_e32 v11, 0x42800000, v11
	v_med3_f32 v9, v10, s10, v46
	v_med3_f32 v10, v11, s10, v46
	v_cvt_pk_fp8_f32 v8, v9, v10 op_sel:[0,0,1]
	ds_read_b32 v9, v30 offset:560
	ds_read_b32 v10, v30 offset:692
	ds_read_b32 v11, v30 offset:824
	ds_read_b32 v12, v30 offset:956
	s_waitcnt lgkmcnt(0)
	v_mul_f32_e32 v9, 0x42800000, v9
	v_mul_f32_e32 v10, 0x42800000, v10
	v_med3_f32 v13, v9, s10, v46
	v_med3_f32 v10, v10, s10, v46
	v_mov_b32_e32 v9, v3
	v_cvt_pk_fp8_f32 v9, v13, v10
	v_mul_f32_e32 v11, 0x42800000, v11
	v_mul_f32_e32 v12, 0x42800000, v12
	v_med3_f32 v10, v11, s10, v46
	v_med3_f32 v11, v12, s10, v46
	v_cvt_pk_fp8_f32 v9, v10, v11 op_sel:[0,0,1]
	v_or_b32_e32 v10, s12, v27
	v_ashrrev_i32_e32 v11, 31, v10
	v_lshlrev_b64 v[10:11], 10, v[10:11]
	v_lshl_add_u64 v[10:11], v[6:7], 0, v[10:11]
	global_store_dwordx2 v[10:11], v[8:9], off
	ds_read_b32 v8, v30 offset:64
	ds_read_b32 v9, v30 offset:196
	ds_read_b32 v10, v30 offset:328
	ds_read_b32 v11, v30 offset:460
	s_waitcnt lgkmcnt(0)
	v_mul_f32_e32 v8, 0x42800000, v8
	v_mul_f32_e32 v9, 0x42800000, v9
	v_med3_f32 v12, v8, s10, v46
	v_med3_f32 v9, v9, s10, v46
	v_mov_b32_e32 v8, v3
	v_cvt_pk_fp8_f32 v8, v12, v9
	v_mul_f32_e32 v10, 0x42800000, v10
	v_mul_f32_e32 v11, 0x42800000, v11
	v_med3_f32 v9, v10, s10, v46
	v_med3_f32 v10, v11, s10, v46
	v_cvt_pk_fp8_f32 v8, v9, v10 op_sel:[0,0,1]
	ds_read_b32 v9, v30 offset:592
	ds_read_b32 v10, v30 offset:724
	ds_read_b32 v11, v30 offset:856
	ds_read_b32 v12, v30 offset:988
	s_waitcnt lgkmcnt(0)
	v_mul_f32_e32 v9, 0x42800000, v9
	v_mul_f32_e32 v10, 0x42800000, v10
	v_med3_f32 v13, v9, s10, v46
	v_med3_f32 v10, v10, s10, v46
	v_mov_b32_e32 v9, v3
	v_cvt_pk_fp8_f32 v9, v13, v10
	v_mul_f32_e32 v11, 0x42800000, v11
	v_mul_f32_e32 v12, 0x42800000, v12
	v_med3_f32 v10, v11, s10, v46
	v_med3_f32 v11, v12, s10, v46
	v_cvt_pk_fp8_f32 v9, v10, v11 op_sel:[0,0,1]
	v_or_b32_e32 v10, s12, v28
	v_ashrrev_i32_e32 v11, 31, v10
	v_lshlrev_b64 v[10:11], 10, v[10:11]
	v_lshl_add_u64 v[10:11], v[6:7], 0, v[10:11]
	global_store_dwordx2 v[10:11], v[8:9], off
	ds_read_b32 v8, v30 offset:96
	ds_read_b32 v9, v30 offset:228
	ds_read_b32 v10, v30 offset:360
	ds_read_b32 v11, v30 offset:492
	s_waitcnt lgkmcnt(0)
	v_mul_f32_e32 v8, 0x42800000, v8
	v_mul_f32_e32 v9, 0x42800000, v9
	v_med3_f32 v12, v8, s10, v46
	v_med3_f32 v9, v9, s10, v46
	v_mov_b32_e32 v8, v3
	v_cvt_pk_fp8_f32 v8, v12, v9
	v_mul_f32_e32 v10, 0x42800000, v10
	v_mul_f32_e32 v11, 0x42800000, v11
	v_med3_f32 v9, v10, s10, v46
	v_med3_f32 v10, v11, s10, v46
	v_cvt_pk_fp8_f32 v8, v9, v10 op_sel:[0,0,1]
	ds_read_b32 v9, v30 offset:624
	ds_read_b32 v10, v30 offset:756
	ds_read_b32 v11, v30 offset:888
	ds_read_b32 v12, v30 offset:1020
	s_waitcnt lgkmcnt(0)
	v_mul_f32_e32 v9, 0x42800000, v9
	v_mul_f32_e32 v10, 0x42800000, v10
	v_med3_f32 v13, v9, s10, v46
	v_med3_f32 v10, v10, s10, v46
	v_mov_b32_e32 v9, v3
	v_cvt_pk_fp8_f32 v9, v13, v10
	v_mul_f32_e32 v11, 0x42800000, v11
	v_mul_f32_e32 v12, 0x42800000, v12
	v_med3_f32 v10, v11, s10, v46
	v_med3_f32 v11, v12, s10, v46
	v_cvt_pk_fp8_f32 v9, v10, v11 op_sel:[0,0,1]
	v_or_b32_e32 v10, s12, v29
	v_ashrrev_i32_e32 v11, 31, v10
	v_lshlrev_b64 v[10:11], 10, v[10:11]
	v_lshl_add_u64 v[6:7], v[6:7], 0, v[10:11]
	global_store_dwordx2 v[6:7], v[8:9], off
	s_waitcnt lgkmcnt(0)
	s_branch .LBB0_1443

.LBB0_1513:
	ds_read_b128 v[152:155], v149
	ds_read_b128 v[156:159], v149 offset:1024
	ds_read_b128 v[160:163], v149 offset:2048
	ds_read_b128 v[164:167], v149 offset:3072
	s_add_u32 s0, s26, 0xfffc0080
	s_addc_u32 s1, s27, -1
	s_cmp_eq_u32 s49, 12
	s_cselect_b32 s31, s21, s1
	s_cselect_b32 s30, s45, s0
	s_cselect_b32 s29, s19, s48
	s_cselect_b32 s28, s46, s47
	v_lshl_add_u64 v[200:201], s[26:27], 0, v[140:141]
	s_add_i32 m0, s10, 0xc000
	ds_read_b128 v[168:171], v150
	ds_read_b128 v[172:175], v150 offset:1024
	ds_read_b128 v[176:179], v150 offset:2048
	ds_read_b128 v[180:183], v150 offset:3072
	ds_read_b128 v[184:187], v150 offset:4096
	ds_read_b128 v[188:191], v150 offset:5120
	ds_read_b128 v[192:195], v150 offset:6144
	ds_read_b128 v[196:199], v150 offset:7168
	global_load_lds_dwordx4 v[200:201], off
	v_lshl_add_u64 v[200:201], s[26:27], 0, v[138:139]
	s_add_i32 m0, s10, 0xe000
	s_nop 0
	global_load_lds_dwordx4 v[200:201], off
	s_waitcnt lgkmcnt(8)
	s_waitcnt vmcnt(10)
	s_barrier
	s_waitcnt lgkmcnt(0)
	s_waitcnt lgkmcnt(0)
	v_mfma_f32_16x16x32_bf16 v[126:129], v[152:155], v[168:171], v[126:129]
	v_mfma_f32_16x16x32_bf16 v[122:125], v[160:163], v[168:171], v[122:125]
	v_mfma_f32_16x16x32_bf16 v[118:121], v[152:155], v[176:179], v[118:121]
	v_mfma_f32_16x16x32_bf16 v[110:113], v[160:163], v[176:179], v[110:113]
	v_mfma_f32_16x16x32_bf16 v[102:105], v[152:155], v[184:187], v[102:105]
	v_mfma_f32_16x16x32_bf16 v[94:97], v[160:163], v[184:187], v[94:97]
	v_mfma_f32_16x16x32_bf16 v[86:89], v[152:155], v[192:195], v[86:89]
	v_mfma_f32_16x16x32_bf16 v[78:81], v[160:163], v[192:195], v[78:81]
	v_mfma_f32_16x16x32_bf16 v[126:129], v[156:159], v[172:175], v[126:129]
	v_mfma_f32_16x16x32_bf16 v[122:125], v[164:167], v[172:175], v[122:125]
	v_mfma_f32_16x16x32_bf16 v[118:121], v[156:159], v[180:183], v[118:121]
	v_mfma_f32_16x16x32_bf16 v[110:113], v[164:167], v[180:183], v[110:113]
	v_mfma_f32_16x16x32_bf16 v[102:105], v[156:159], v[188:191], v[102:105]
	v_mfma_f32_16x16x32_bf16 v[94:97], v[164:167], v[188:191], v[94:97]
	v_mfma_f32_16x16x32_bf16 v[86:89], v[156:159], v[196:199], v[86:89]
	v_mfma_f32_16x16x32_bf16 v[78:81], v[164:167], v[196:199], v[78:81]
	s_barrier
	s_add_i32 s0, s42, s9
	v_lshl_add_u64 v[216:217], s[28:29], 0, v[134:135]
	s_mov_b32 m0, s0
	ds_read_b128 v[200:203], v151
	ds_read_b128 v[204:207], v151 offset:1024
	ds_read_b128 v[208:211], v151 offset:2048
	ds_read_b128 v[212:215], v151 offset:3072
	global_load_lds_dwordx4 v[216:217], off
	v_lshl_add_u64 v[218:219], s[28:29], 0, v[130:131]
	s_add_i32 m0, s0, 0x2000
	s_nop 0
	global_load_lds_dwordx4 v[218:219], off
	s_waitcnt vmcnt(10)
	s_barrier
	s_waitcnt lgkmcnt(0)
	s_waitcnt lgkmcnt(0)
	v_mfma_f32_16x16x32_bf16 v[114:117], v[200:203], v[168:171], v[114:117]
	v_mfma_f32_16x16x32_bf16 v[106:109], v[208:211], v[168:171], v[106:109]
	v_mfma_f32_16x16x32_bf16 v[98:101], v[200:203], v[176:179], v[98:101]
	v_mfma_f32_16x16x32_bf16 v[90:93], v[208:211], v[176:179], v[90:93]
	v_mfma_f32_16x16x32_bf16 v[82:85], v[200:203], v[184:187], v[82:85]
	v_mfma_f32_16x16x32_bf16 v[74:77], v[208:211], v[184:187], v[74:77]
	v_mfma_f32_16x16x32_bf16 v[70:73], v[200:203], v[192:195], v[70:73]
	v_mfma_f32_16x16x32_bf16 v[66:69], v[208:211], v[192:195], v[66:69]
	v_mfma_f32_16x16x32_bf16 v[114:117], v[204:207], v[172:175], v[114:117]
	v_mfma_f32_16x16x32_bf16 v[106:109], v[212:215], v[172:175], v[106:109]
	v_mfma_f32_16x16x32_bf16 v[98:101], v[204:207], v[180:183], v[98:101]
	v_mfma_f32_16x16x32_bf16 v[90:93], v[212:215], v[180:183], v[90:93]
	v_mfma_f32_16x16x32_bf16 v[82:85], v[204:207], v[188:191], v[82:85]
	v_mfma_f32_16x16x32_bf16 v[74:77], v[212:215], v[188:191], v[74:77]
	v_mfma_f32_16x16x32_bf16 v[70:73], v[204:207], v[196:199], v[70:73]
	v_mfma_f32_16x16x32_bf16 v[66:69], v[212:215], v[196:199], v[66:69]
	s_mov_b32 m0, s10
	v_lshl_add_u64 v[220:221], s[30:31], 0, v[136:137]
	s_barrier
	ds_read_b128 v[168:171], v150 offset:16384
	ds_read_b128 v[172:175], v150 offset:17408
	ds_read_b128 v[176:179], v150 offset:18432
	ds_read_b128 v[180:183], v150 offset:19456
	ds_read_b128 v[184:187], v150 offset:20480
	ds_read_b128 v[188:191], v150 offset:21504
	ds_read_b128 v[192:195], v150 offset:22528
	ds_read_b128 v[196:199], v150 offset:23552
	global_load_lds_dwordx4 v[220:221], off
	v_lshl_add_u64 v[222:223], s[30:31], 0, v[132:133]
	s_mov_b32 m0, s11
	s_nop 0
	global_load_lds_dwordx4 v[222:223], off
	s_waitcnt vmcnt(10)
	s_barrier
	s_waitcnt lgkmcnt(0)
	s_waitcnt lgkmcnt(0)
	v_mfma_f32_16x16x32_bf16 v[62:65], v[152:155], v[168:171], v[62:65]
	v_mfma_f32_16x16x32_bf16 v[58:61], v[160:163], v[168:171], v[58:61]
	v_mfma_f32_16x16x32_bf16 v[54:57], v[152:155], v[176:179], v[54:57]
	v_mfma_f32_16x16x32_bf16 v[50:53], v[160:163], v[176:179], v[50:53]
	v_mfma_f32_16x16x32_bf16 v[38:41], v[152:155], v[184:187], v[38:41]
	v_mfma_f32_16x16x32_bf16 v[34:37], v[160:163], v[184:187], v[34:37]
	v_mfma_f32_16x16x32_bf16 v[22:25], v[152:155], v[192:195], v[22:25]
	v_mfma_f32_16x16x32_bf16 v[18:21], v[160:163], v[192:195], v[18:21]
	v_mfma_f32_16x16x32_bf16 v[62:65], v[156:159], v[172:175], v[62:65]
	v_mfma_f32_16x16x32_bf16 v[58:61], v[164:167], v[172:175], v[58:61]
	v_mfma_f32_16x16x32_bf16 v[54:57], v[156:159], v[180:183], v[54:57]
	v_mfma_f32_16x16x32_bf16 v[50:53], v[164:167], v[180:183], v[50:53]
	v_mfma_f32_16x16x32_bf16 v[38:41], v[156:159], v[188:191], v[38:41]
	v_mfma_f32_16x16x32_bf16 v[34:37], v[164:167], v[188:191], v[34:37]
	v_mfma_f32_16x16x32_bf16 v[22:25], v[156:159], v[196:199], v[22:25]
	v_mfma_f32_16x16x32_bf16 v[18:21], v[164:167], v[196:199], v[18:21]
	s_barrier
	s_add_u32 s0, s28, 0x40000
	s_addc_u32 s1, s29, 0
	s_add_i32 s50, s43, s9
	v_lshl_add_u64 v[152:153], s[0:1], 0, v[134:135]
	s_mov_b32 m0, s50
	s_nop 0
	global_load_lds_dwordx4 v[152:153], off
	v_lshl_add_u64 v[152:153], s[0:1], 0, v[130:131]
	s_add_i32 m0, s50, 0x2000
	s_nop 0
	global_load_lds_dwordx4 v[152:153], off
	s_waitcnt vmcnt(10)
	s_barrier
	v_mfma_f32_16x16x32_bf16 v[46:49], v[200:203], v[168:171], v[46:49]
	v_mfma_f32_16x16x32_bf16 v[42:45], v[208:211], v[168:171], v[42:45]
	v_mfma_f32_16x16x32_bf16 v[30:33], v[200:203], v[176:179], v[30:33]
	v_mfma_f32_16x16x32_bf16 v[26:29], v[208:211], v[176:179], v[26:29]
	v_mfma_f32_16x16x32_bf16 v[14:17], v[200:203], v[184:187], v[14:17]
	v_mfma_f32_16x16x32_bf16 v[10:13], v[208:211], v[184:187], v[10:13]
	v_mfma_f32_16x16x32_bf16 v[6:9], v[200:203], v[192:195], v[6:9]
	v_mfma_f32_16x16x32_bf16 v[2:5], v[208:211], v[192:195], v[2:5]
	v_mfma_f32_16x16x32_bf16 v[46:49], v[204:207], v[172:175], v[46:49]
	v_mfma_f32_16x16x32_bf16 v[42:45], v[212:215], v[172:175], v[42:45]
	v_mfma_f32_16x16x32_bf16 v[30:33], v[204:207], v[180:183], v[30:33]
	v_mfma_f32_16x16x32_bf16 v[26:29], v[212:215], v[180:183], v[26:29]
	v_mfma_f32_16x16x32_bf16 v[14:17], v[204:207], v[188:191], v[14:17]
	v_mfma_f32_16x16x32_bf16 v[10:13], v[212:215], v[188:191], v[10:13]
	v_mfma_f32_16x16x32_bf16 v[6:9], v[204:207], v[196:199], v[6:9]
	v_mfma_f32_16x16x32_bf16 v[2:5], v[212:215], v[196:199], v[2:5]
	s_add_i32 s50, 0, 0x18000
	v_add_u32_e32 v164, s50, v148
	s_barrier
	ds_read_b128 v[152:155], v164
	ds_read_b128 v[156:159], v164 offset:1024
	ds_read_b128 v[160:163], v164 offset:2048
	ds_read_b128 v[164:167], v164 offset:3072
	s_add_u32 s0, s30, 0x40000
	s_addc_u32 s1, s31, 0
	s_mov_b32 m0, s17
	v_lshl_add_u64 v[200:201], s[0:1], 0, v[136:137]
	ds_read_b128 v[168:171], v150 offset:32768
	ds_read_b128 v[172:175], v150 offset:33792
	ds_read_b128 v[176:179], v150 offset:34816
	ds_read_b128 v[180:183], v150 offset:35840
	ds_read_b128 v[184:187], v150 offset:36864
	ds_read_b128 v[188:191], v150 offset:37888
	ds_read_b128 v[192:195], v150 offset:38912
	ds_read_b128 v[196:199], v150 offset:39936
	global_load_lds_dwordx4 v[200:201], off
	v_lshl_add_u64 v[200:201], s[0:1], 0, v[132:133]
	s_mov_b32 m0, s34
	s_nop 0
	global_load_lds_dwordx4 v[200:201], off
	s_waitcnt lgkmcnt(8)
	s_waitcnt vmcnt(10)
	s_barrier
	s_waitcnt lgkmcnt(0)
	s_waitcnt lgkmcnt(0)
	v_mfma_f32_16x16x32_bf16 v[126:129], v[152:155], v[168:171], v[126:129]
	v_mfma_f32_16x16x32_bf16 v[122:125], v[160:163], v[168:171], v[122:125]
	v_mfma_f32_16x16x32_bf16 v[118:121], v[152:155], v[176:179], v[118:121]
	v_mfma_f32_16x16x32_bf16 v[110:113], v[160:163], v[176:179], v[110:113]
	v_mfma_f32_16x16x32_bf16 v[102:105], v[152:155], v[184:187], v[102:105]
	v_mfma_f32_16x16x32_bf16 v[94:97], v[160:163], v[184:187], v[94:97]
	v_mfma_f32_16x16x32_bf16 v[86:89], v[152:155], v[192:195], v[86:89]
	v_mfma_f32_16x16x32_bf16 v[78:81], v[160:163], v[192:195], v[78:81]
	v_mfma_f32_16x16x32_bf16 v[126:129], v[156:159], v[172:175], v[126:129]
	v_mfma_f32_16x16x32_bf16 v[122:125], v[164:167], v[172:175], v[122:125]
	v_mfma_f32_16x16x32_bf16 v[118:121], v[156:159], v[180:183], v[118:121]
	v_mfma_f32_16x16x32_bf16 v[110:113], v[164:167], v[180:183], v[110:113]
	v_mfma_f32_16x16x32_bf16 v[102:105], v[156:159], v[188:191], v[102:105]
	v_mfma_f32_16x16x32_bf16 v[94:97], v[164:167], v[188:191], v[94:97]
	v_mfma_f32_16x16x32_bf16 v[86:89], v[156:159], v[196:199], v[86:89]
	v_mfma_f32_16x16x32_bf16 v[78:81], v[164:167], v[196:199], v[78:81]
	s_barrier
	s_add_i32 s30, 0, 0x1c000
	s_add_i32 s0, s50, s9
	v_add_u32_e32 v212, s30, v148
	v_lshl_add_u64 v[216:217], v[216:217], 0, s[14:15]
	s_mov_b32 m0, s0
	ds_read_b128 v[200:203], v212
	ds_read_b128 v[204:207], v212 offset:1024
	ds_read_b128 v[208:211], v212 offset:2048
	ds_read_b128 v[212:215], v212 offset:3072
	global_load_lds_dwordx4 v[216:217], off
	v_lshl_add_u64 v[216:217], v[218:219], 0, s[14:15]
	s_add_i32 m0, s0, 0x2000
	s_nop 0
	global_load_lds_dwordx4 v[216:217], off
	s_waitcnt vmcnt(10)
	s_barrier
	s_waitcnt lgkmcnt(0)
	s_waitcnt lgkmcnt(0)
	v_mfma_f32_16x16x32_bf16 v[114:117], v[200:203], v[168:171], v[114:117]
	v_mfma_f32_16x16x32_bf16 v[106:109], v[208:211], v[168:171], v[106:109]
	v_mfma_f32_16x16x32_bf16 v[98:101], v[200:203], v[176:179], v[98:101]
	v_mfma_f32_16x16x32_bf16 v[90:93], v[208:211], v[176:179], v[90:93]
	v_mfma_f32_16x16x32_bf16 v[82:85], v[200:203], v[184:187], v[82:85]
	v_mfma_f32_16x16x32_bf16 v[74:77], v[208:211], v[184:187], v[74:77]
	v_mfma_f32_16x16x32_bf16 v[70:73], v[200:203], v[192:195], v[70:73]
	v_mfma_f32_16x16x32_bf16 v[66:69], v[208:211], v[192:195], v[66:69]
	v_mfma_f32_16x16x32_bf16 v[114:117], v[204:207], v[172:175], v[114:117]
	v_mfma_f32_16x16x32_bf16 v[106:109], v[212:215], v[172:175], v[106:109]
	v_mfma_f32_16x16x32_bf16 v[98:101], v[204:207], v[180:183], v[98:101]
	v_mfma_f32_16x16x32_bf16 v[90:93], v[212:215], v[180:183], v[90:93]
	v_mfma_f32_16x16x32_bf16 v[82:85], v[204:207], v[188:191], v[82:85]
	v_mfma_f32_16x16x32_bf16 v[74:77], v[212:215], v[188:191], v[74:77]
	v_mfma_f32_16x16x32_bf16 v[70:73], v[204:207], v[196:199], v[70:73]
	v_mfma_f32_16x16x32_bf16 v[66:69], v[212:215], v[196:199], v[66:69]
	s_mov_b32 m0, s40
	v_lshl_add_u64 v[216:217], v[220:221], 0, s[14:15]
	s_barrier
	ds_read_b128 v[168:171], v150 offset:49152
	ds_read_b128 v[172:175], v150 offset:50176
	ds_read_b128 v[176:179], v150 offset:51200
	ds_read_b128 v[180:183], v150 offset:52224
	ds_read_b128 v[184:187], v150 offset:53248
	ds_read_b128 v[188:191], v150 offset:54272
	ds_read_b128 v[192:195], v150 offset:55296
	ds_read_b128 v[196:199], v150 offset:56320
	global_load_lds_dwordx4 v[216:217], off
	v_lshl_add_u64 v[216:217], v[222:223], 0, s[14:15]
	s_mov_b32 m0, s41
	s_nop 0
	global_load_lds_dwordx4 v[216:217], off
	s_waitcnt vmcnt(10)
	s_barrier
	s_waitcnt lgkmcnt(0)
	s_waitcnt lgkmcnt(0)
	v_mfma_f32_16x16x32_bf16 v[62:65], v[152:155], v[168:171], v[62:65]
	v_mfma_f32_16x16x32_bf16 v[58:61], v[160:163], v[168:171], v[58:61]
	v_mfma_f32_16x16x32_bf16 v[54:57], v[152:155], v[176:179], v[54:57]
	v_mfma_f32_16x16x32_bf16 v[50:53], v[160:163], v[176:179], v[50:53]
	v_mfma_f32_16x16x32_bf16 v[38:41], v[152:155], v[184:187], v[38:41]
	v_mfma_f32_16x16x32_bf16 v[34:37], v[160:163], v[184:187], v[34:37]
	v_mfma_f32_16x16x32_bf16 v[22:25], v[152:155], v[192:195], v[22:25]
	v_mfma_f32_16x16x32_bf16 v[18:21], v[160:163], v[192:195], v[18:21]
	v_mfma_f32_16x16x32_bf16 v[62:65], v[156:159], v[172:175], v[62:65]
	v_mfma_f32_16x16x32_bf16 v[58:61], v[164:167], v[172:175], v[58:61]
	v_mfma_f32_16x16x32_bf16 v[54:57], v[156:159], v[180:183], v[54:57]
	v_mfma_f32_16x16x32_bf16 v[50:53], v[164:167], v[180:183], v[50:53]
	v_mfma_f32_16x16x32_bf16 v[38:41], v[156:159], v[188:191], v[38:41]
	v_mfma_f32_16x16x32_bf16 v[34:37], v[164:167], v[188:191], v[34:37]
	v_mfma_f32_16x16x32_bf16 v[22:25], v[156:159], v[196:199], v[22:25]
	v_mfma_f32_16x16x32_bf16 v[18:21], v[164:167], v[196:199], v[18:21]
	s_barrier
	s_add_u32 s0, s28, 0x40080
	s_addc_u32 s1, s29, 0
	s_add_i32 s28, s30, s9
	v_lshl_add_u64 v[152:153], s[0:1], 0, v[134:135]
	s_mov_b32 m0, s28
	s_nop 0
	global_load_lds_dwordx4 v[152:153], off
	v_lshl_add_u64 v[152:153], s[0:1], 0, v[130:131]
	s_add_i32 m0, s28, 0x2000
	s_nop 0
	global_load_lds_dwordx4 v[152:153], off
	s_waitcnt vmcnt(10)
	s_barrier
	v_mfma_f32_16x16x32_bf16 v[46:49], v[200:203], v[168:171], v[46:49]
	v_mfma_f32_16x16x32_bf16 v[42:45], v[208:211], v[168:171], v[42:45]
	v_mfma_f32_16x16x32_bf16 v[30:33], v[200:203], v[176:179], v[30:33]
	v_mfma_f32_16x16x32_bf16 v[26:29], v[208:211], v[176:179], v[26:29]
	v_mfma_f32_16x16x32_bf16 v[14:17], v[200:203], v[184:187], v[14:17]
	v_mfma_f32_16x16x32_bf16 v[10:13], v[208:211], v[184:187], v[10:13]
	v_mfma_f32_16x16x32_bf16 v[6:9], v[200:203], v[192:195], v[6:9]
	v_mfma_f32_16x16x32_bf16 v[2:5], v[208:211], v[192:195], v[2:5]
	v_mfma_f32_16x16x32_bf16 v[46:49], v[204:207], v[172:175], v[46:49]
	v_mfma_f32_16x16x32_bf16 v[42:45], v[212:215], v[172:175], v[42:45]
	v_mfma_f32_16x16x32_bf16 v[30:33], v[204:207], v[180:183], v[30:33]
	v_mfma_f32_16x16x32_bf16 v[26:29], v[212:215], v[180:183], v[26:29]
	v_mfma_f32_16x16x32_bf16 v[14:17], v[204:207], v[188:191], v[14:17]
	v_mfma_f32_16x16x32_bf16 v[10:13], v[212:215], v[188:191], v[10:13]
	v_mfma_f32_16x16x32_bf16 v[6:9], v[204:207], v[196:199], v[6:9]
	v_mfma_f32_16x16x32_bf16 v[2:5], v[212:215], v[196:199], v[2:5]
	s_add_i32 s49, s49, 2
	s_add_u32 s47, s47, 0x100
	s_addc_u32 s48, s48, 0
	s_add_u32 s26, s26, 0x100
	s_addc_u32 s27, s27, 0
	s_cmp_gt_u32 s49, 13
	s_barrier
	s_cbranch_scc0 .LBB0_1513
	v_mov_b32_e32 v152, v146
	v_mov_b32_e32 v153, v147
	s_cmp_gt_i32 s44, 7
	s_cbranch_scc1 .LBB0_1505
	s_ashr_i32 s0, s44, 31
	s_lshr_b32 s0, s0, 30
	s_add_i32 s0, s44, s0
	s_ashr_i32 s0, s0, 2
	s_ashr_i32 s1, s0, 31
	s_lshl_b32 s19, s44, 8
	s_lshl_b64 s[26:27], s[0:1], 27
	s_add_u32 s26, s36, s26
	s_addc_u32 s27, s37, s27
	s_or_b32 s1, s19, s39
	s_lshl_b32 s0, s0, 10
	s_sub_i32 s0, s1, s0
	v_lshl_add_u32 v154, v153, 3, s0
	s_lshl_b32 s0, s16, 8
	s_add_i32 s0, s0, s38
	v_add_u32_e32 v156, s0, v152
	v_mov_b32_e32 v152, v156
	v_ashrrev_i32_e32 v155, 31, v154
	v_lshl_add_u64 v[154:155], v[154:155], 1, s[26:27]
	v_ashrrev_i32_e32 v153, 31, v152
	v_lshlrev_b64 v[152:153], 11, v[152:153]
	v_lshl_add_u64 v[152:153], v[154:155], 0, v[152:153]
	v_cvt_pk_bf16_f32 v126, v126, v127
	v_cvt_pk_bf16_f32 v127, v128, v129
	v_cvt_pk_bf16_f32 v128, v122, v123
	v_cvt_pk_bf16_f32 v129, v124, v125
	v_cvt_pk_bf16_f32 v114, v114, v115
	v_cvt_pk_bf16_f32 v115, v116, v117
	v_cvt_pk_bf16_f32 v116, v106, v107
	v_cvt_pk_bf16_f32 v117, v108, v109
	v_add_u32_e32 v106, 16, v156
	global_store_dwordx4 v[152:153], v[126:129], off
	global_store_dwordx4 v[152:153], v[114:117], off offset:256
	v_cvt_pk_bf16_f32 v108, v110, v111
	v_ashrrev_i32_e32 v107, 31, v106
	v_lshlrev_b64 v[106:107], 11, v[106:107]
	v_lshl_add_u64 v[114:115], v[154:155], 0, v[106:107]
	v_cvt_pk_bf16_f32 v106, v118, v119
	v_cvt_pk_bf16_f32 v107, v120, v121
	v_cvt_pk_bf16_f32 v109, v112, v113
	v_cvt_pk_bf16_f32 v98, v98, v99
	v_cvt_pk_bf16_f32 v99, v100, v101
	v_cvt_pk_bf16_f32 v100, v90, v91
	v_cvt_pk_bf16_f32 v101, v92, v93
	v_add_u32_e32 v90, 32, v156
	global_store_dwordx4 v[114:115], v[106:109], off
	global_store_dwordx4 v[114:115], v[98:101], off offset:256
	v_cvt_pk_bf16_f32 v92, v94, v95
	v_ashrrev_i32_e32 v91, 31, v90
	v_lshlrev_b64 v[90:91], 11, v[90:91]
	v_lshl_add_u64 v[98:99], v[154:155], 0, v[90:91]
	v_cvt_pk_bf16_f32 v90, v102, v103
	v_cvt_pk_bf16_f32 v91, v104, v105
	v_cvt_pk_bf16_f32 v93, v96, v97
	v_cvt_pk_bf16_f32 v82, v82, v83
	v_cvt_pk_bf16_f32 v83, v84, v85
	v_cvt_pk_bf16_f32 v84, v74, v75
	v_cvt_pk_bf16_f32 v85, v76, v77
	v_add_u32_e32 v74, 48, v156
	global_store_dwordx4 v[98:99], v[90:93], off
	global_store_dwordx4 v[98:99], v[82:85], off offset:256
	v_cvt_pk_bf16_f32 v76, v78, v79
	v_ashrrev_i32_e32 v75, 31, v74
	v_lshlrev_b64 v[74:75], 11, v[74:75]
	v_lshl_add_u64 v[82:83], v[154:155], 0, v[74:75]
	v_cvt_pk_bf16_f32 v74, v86, v87
	v_cvt_pk_bf16_f32 v75, v88, v89
	v_cvt_pk_bf16_f32 v77, v80, v81
	v_cvt_pk_bf16_f32 v70, v70, v71
	v_cvt_pk_bf16_f32 v71, v72, v73
	v_cvt_pk_bf16_f32 v72, v66, v67
	v_cvt_pk_bf16_f32 v73, v68, v69
	v_add_u32_e32 v66, 0x80, v156
	global_store_dwordx4 v[82:83], v[74:77], off
	global_store_dwordx4 v[82:83], v[70:73], off offset:256
	v_cvt_pk_bf16_f32 v62, v62, v63
	v_ashrrev_i32_e32 v67, 31, v66
	v_lshlrev_b64 v[66:67], 11, v[66:67]
	v_lshl_add_u64 v[66:67], v[154:155], 0, v[66:67]
	v_cvt_pk_bf16_f32 v63, v64, v65
	v_cvt_pk_bf16_f32 v64, v58, v59
	v_cvt_pk_bf16_f32 v65, v60, v61
	v_cvt_pk_bf16_f32 v46, v46, v47
	v_cvt_pk_bf16_f32 v47, v48, v49
	v_cvt_pk_bf16_f32 v48, v42, v43
	v_cvt_pk_bf16_f32 v49, v44, v45
	v_add_u32_e32 v42, 0x90, v156
	global_store_dwordx4 v[66:67], v[62:65], off
	global_store_dwordx4 v[66:67], v[46:49], off offset:256
	v_cvt_pk_bf16_f32 v44, v50, v51
	v_ashrrev_i32_e32 v43, 31, v42
	v_lshlrev_b64 v[42:43], 11, v[42:43]
	v_lshl_add_u64 v[46:47], v[154:155], 0, v[42:43]
	v_cvt_pk_bf16_f32 v42, v54, v55
	v_cvt_pk_bf16_f32 v43, v56, v57
	v_cvt_pk_bf16_f32 v45, v52, v53
	v_cvt_pk_bf16_f32 v30, v30, v31
	v_cvt_pk_bf16_f32 v31, v32, v33
	v_cvt_pk_bf16_f32 v32, v26, v27
	v_cvt_pk_bf16_f32 v33, v28, v29
	v_add_u32_e32 v26, 0xa0, v156
	global_store_dwordx4 v[46:47], v[42:45], off
	global_store_dwordx4 v[46:47], v[30:33], off offset:256
	v_cvt_pk_bf16_f32 v28, v34, v35
	v_ashrrev_i32_e32 v27, 31, v26
	v_lshlrev_b64 v[26:27], 11, v[26:27]
	v_lshl_add_u64 v[30:31], v[154:155], 0, v[26:27]
	v_cvt_pk_bf16_f32 v26, v38, v39
	v_cvt_pk_bf16_f32 v27, v40, v41
	v_cvt_pk_bf16_f32 v29, v36, v37
	v_cvt_pk_bf16_f32 v14, v14, v15
	v_cvt_pk_bf16_f32 v15, v16, v17
	v_cvt_pk_bf16_f32 v16, v10, v11
	v_cvt_pk_bf16_f32 v17, v12, v13
	v_add_u32_e32 v10, 0xb0, v156
	global_store_dwordx4 v[30:31], v[26:29], off
	global_store_dwordx4 v[30:31], v[14:17], off offset:256
	v_cvt_pk_bf16_f32 v12, v18, v19
	v_ashrrev_i32_e32 v11, 31, v10
	v_lshlrev_b64 v[10:11], 11, v[10:11]
	v_lshl_add_u64 v[14:15], v[154:155], 0, v[10:11]
	v_cvt_pk_bf16_f32 v10, v22, v23
	v_cvt_pk_bf16_f32 v11, v24, v25
	v_cvt_pk_bf16_f32 v13, v20, v21
	v_cvt_pk_bf16_f32 v6, v6, v7
	v_cvt_pk_bf16_f32 v7, v8, v9
	v_cvt_pk_bf16_f32 v8, v2, v3
	v_cvt_pk_bf16_f32 v9, v4, v5
	global_store_dwordx4 v[14:15], v[10:13], off
	global_store_dwordx4 v[14:15], v[6:9], off offset:256
	s_branch .LBB0_1505

.LBB0_1575:
	s_or_b64 exec, exec, s[16:17]
	s_waitcnt vmcnt(0) lgkmcnt(0)
	v_lshlrev_b32_e32 v158, 16, v114
	v_and_b32_e32 v159, 0xffff0000, v114
	v_lshlrev_b32_e32 v114, 16, v115
	v_and_b32_e32 v115, 0xffff0000, v115
	v_pk_fma_f32 v[158:159], v[6:7], v[158:159], v[38:39]
	v_pk_fma_f32 v[114:115], v[8:9], v[114:115], v[40:41]
	v_lshlrev_b32_e32 v160, 16, v116
	v_and_b32_e32 v161, 0xffff0000, v116
	v_lshlrev_b32_e32 v116, 16, v117
	v_and_b32_e32 v117, 0xffff0000, v117
	v_lshlrev_b32_e32 v162, 16, v110
	v_and_b32_e32 v163, 0xffff0000, v110
	v_lshlrev_b32_e32 v110, 16, v111
	v_and_b32_e32 v111, 0xffff0000, v111
	v_pk_fma_f32 v[160:161], v[2:3], v[160:161], v[34:35]
	v_pk_fma_f32 v[116:117], v[4:5], v[116:117], v[36:37]
	v_pk_fma_f32 v[114:115], v[12:13], v[110:111], v[114:115]
	v_pk_fma_f32 v[158:159], v[10:11], v[162:163], v[158:159]
	v_lshlrev_b32_e32 v164, 16, v112
	v_and_b32_e32 v165, 0xffff0000, v112
	v_lshlrev_b32_e32 v112, 16, v113
	v_and_b32_e32 v113, 0xffff0000, v113
	v_lshlrev_b32_e32 v166, 16, v106
	v_and_b32_e32 v167, 0xffff0000, v106
	v_lshlrev_b32_e32 v106, 16, v107
	v_and_b32_e32 v107, 0xffff0000, v107
	v_pk_fma_f32 v[116:117], v[16:17], v[112:113], v[116:117]
	v_pk_fma_f32 v[160:161], v[14:15], v[164:165], v[160:161]
	v_pk_fma_f32 v[158:159], v[18:19], v[166:167], v[158:159]
	v_pk_fma_f32 v[114:115], v[20:21], v[106:107], v[114:115]
	v_lshlrev_b32_e32 v168, 16, v108
	v_and_b32_e32 v169, 0xffff0000, v108
	v_lshlrev_b32_e32 v108, 16, v109
	v_and_b32_e32 v109, 0xffff0000, v109
	v_lshlrev_b32_e32 v170, 16, v102
	v_and_b32_e32 v171, 0xffff0000, v102
	v_lshlrev_b32_e32 v172, 16, v103
	v_and_b32_e32 v173, 0xffff0000, v103
	v_pk_fma_f32 v[160:161], v[22:23], v[168:169], v[160:161]
	v_pk_fma_f32 v[116:117], v[24:25], v[108:109], v[116:117]
	v_pk_fma_f32 v[114:115], v[28:29], v[172:173], v[114:115]
	v_pk_fma_f32 v[102:103], v[26:27], v[170:171], v[158:159]
	v_lshlrev_b32_e32 v158, 16, v104
	v_and_b32_e32 v159, 0xffff0000, v104
	v_lshlrev_b32_e32 v174, 16, v105
	v_and_b32_e32 v175, 0xffff0000, v105
	v_ashrrev_i32_e32 v125, 31, v124
	v_pk_fma_f32 v[116:117], v[32:33], v[174:175], v[116:117]
	v_pk_fma_f32 v[104:105], v[30:31], v[158:159], v[160:161]
	v_cvt_pk_bf16_f32 v102, v102, v103
	v_cvt_pk_bf16_f32 v103, v114, v115
	v_lshlrev_b64 v[114:115], 11, v[124:125]
	v_cvt_pk_bf16_f32 v104, v104, v105
	v_cvt_pk_bf16_f32 v105, v116, v117
	v_lshl_add_u64 v[114:115], v[122:123], 0, v[114:115]
	global_store_dwordx4 v[114:115], v[102:105], off
	v_pk_fma_f32 v[112:113], v[4:5], v[112:113], v[36:37]
	v_lshlrev_b32_e32 v114, 16, v98
	v_pk_fma_f32 v[102:103], v[6:7], v[162:163], v[38:39]
	v_pk_fma_f32 v[104:105], v[8:9], v[110:111], v[40:41]
	v_pk_fma_f32 v[110:111], v[2:3], v[164:165], v[34:35]
	v_pk_fma_f32 v[104:105], v[12:13], v[106:107], v[104:105]
	v_pk_fma_f32 v[102:103], v[10:11], v[166:167], v[102:103]
	v_pk_fma_f32 v[112:113], v[16:17], v[108:109], v[112:113]
	v_pk_fma_f32 v[110:111], v[14:15], v[168:169], v[110:111]
	v_pk_fma_f32 v[102:103], v[18:19], v[170:171], v[102:103]
	v_pk_fma_f32 v[104:105], v[20:21], v[172:173], v[104:105]
	v_and_b32_e32 v115, 0xffff0000, v98
	v_lshlrev_b32_e32 v116, 16, v99
	v_and_b32_e32 v117, 0xffff0000, v99
	v_pk_fma_f32 v[110:111], v[22:23], v[158:159], v[110:111]
	v_pk_fma_f32 v[112:113], v[24:25], v[174:175], v[112:113]
	v_pk_fma_f32 v[104:105], v[28:29], v[116:117], v[104:105]
	v_pk_fma_f32 v[98:99], v[26:27], v[114:115], v[102:103]
	v_lshlrev_b32_e32 v102, 16, v100
	v_and_b32_e32 v103, 0xffff0000, v100
	v_lshlrev_b32_e32 v160, 16, v101
	v_and_b32_e32 v161, 0xffff0000, v101
	v_ashrrev_i32_e32 v155, 31, v154
	v_pk_fma_f32 v[112:113], v[32:33], v[160:161], v[112:113]
	v_pk_fma_f32 v[100:101], v[30:31], v[102:103], v[110:111]
	v_cvt_pk_bf16_f32 v98, v98, v99
	v_cvt_pk_bf16_f32 v99, v104, v105
	v_lshlrev_b64 v[104:105], 11, v[154:155]
	v_cvt_pk_bf16_f32 v100, v100, v101
	v_cvt_pk_bf16_f32 v101, v112, v113
	v_lshl_add_u64 v[104:105], v[122:123], 0, v[104:105]
	global_store_dwordx4 v[104:105], v[98:101], off
	v_pk_fma_f32 v[104:105], v[2:3], v[168:169], v[34:35]
	v_lshlrev_b32_e32 v110, 16, v95
	v_pk_fma_f32 v[98:99], v[6:7], v[166:167], v[38:39]
	v_pk_fma_f32 v[100:101], v[8:9], v[106:107], v[40:41]
	v_pk_fma_f32 v[106:107], v[4:5], v[108:109], v[36:37]
	v_pk_fma_f32 v[100:101], v[12:13], v[172:173], v[100:101]
	v_pk_fma_f32 v[98:99], v[10:11], v[170:171], v[98:99]
	v_pk_fma_f32 v[106:107], v[16:17], v[174:175], v[106:107]
	v_pk_fma_f32 v[104:105], v[14:15], v[158:159], v[104:105]
	v_pk_fma_f32 v[98:99], v[18:19], v[114:115], v[98:99]
	v_pk_fma_f32 v[100:101], v[20:21], v[116:117], v[100:101]
	v_lshlrev_b32_e32 v108, 16, v94
	v_and_b32_e32 v109, 0xffff0000, v94
	v_and_b32_e32 v111, 0xffff0000, v95
	v_pk_fma_f32 v[104:105], v[22:23], v[102:103], v[104:105]
	v_pk_fma_f32 v[106:107], v[24:25], v[160:161], v[106:107]
	v_pk_fma_f32 v[100:101], v[28:29], v[110:111], v[100:101]
	v_pk_fma_f32 v[94:95], v[26:27], v[108:109], v[98:99]
	v_lshlrev_b32_e32 v98, 16, v96
	v_and_b32_e32 v99, 0xffff0000, v96
	v_lshlrev_b32_e32 v112, 16, v97
	v_and_b32_e32 v113, 0xffff0000, v97
	v_ashrrev_i32_e32 v153, 31, v152
	v_pk_fma_f32 v[106:107], v[32:33], v[112:113], v[106:107]
	v_pk_fma_f32 v[96:97], v[30:31], v[98:99], v[104:105]
	v_cvt_pk_bf16_f32 v94, v94, v95
	v_cvt_pk_bf16_f32 v95, v100, v101
	v_lshlrev_b64 v[100:101], 11, v[152:153]
	v_cvt_pk_bf16_f32 v96, v96, v97
	v_cvt_pk_bf16_f32 v97, v106, v107
	v_lshl_add_u64 v[100:101], v[122:123], 0, v[100:101]
	global_store_dwordx4 v[100:101], v[94:97], off
	v_pk_fma_f32 v[100:101], v[2:3], v[158:159], v[34:35]
	v_pk_fma_f32 v[104:105], v[4:5], v[174:175], v[36:37]
	v_pk_fma_f32 v[94:95], v[6:7], v[170:171], v[38:39]
	v_pk_fma_f32 v[96:97], v[8:9], v[172:173], v[40:41]
	v_pk_fma_f32 v[94:95], v[10:11], v[114:115], v[94:95]
	v_pk_fma_f32 v[96:97], v[12:13], v[116:117], v[96:97]
	v_pk_fma_f32 v[104:105], v[16:17], v[160:161], v[104:105]
	v_pk_fma_f32 v[100:101], v[14:15], v[102:103], v[100:101]
	v_pk_fma_f32 v[94:95], v[18:19], v[108:109], v[94:95]
	v_pk_fma_f32 v[96:97], v[20:21], v[110:111], v[96:97]
	v_lshlrev_b32_e32 v106, 16, v90
	v_and_b32_e32 v107, 0xffff0000, v90
	v_lshlrev_b32_e32 v152, 16, v91
	v_and_b32_e32 v153, 0xffff0000, v91
	v_pk_fma_f32 v[100:101], v[22:23], v[98:99], v[100:101]
	v_pk_fma_f32 v[104:105], v[24:25], v[112:113], v[104:105]
	v_pk_fma_f32 v[96:97], v[28:29], v[152:153], v[96:97]
	v_pk_fma_f32 v[90:91], v[26:27], v[106:107], v[94:95]
	v_lshlrev_b32_e32 v94, 16, v92
	v_and_b32_e32 v95, 0xffff0000, v92
	v_lshlrev_b32_e32 v154, 16, v93
	v_and_b32_e32 v155, 0xffff0000, v93
	v_ashrrev_i32_e32 v151, 31, v150
	v_pk_fma_f32 v[104:105], v[32:33], v[154:155], v[104:105]
	v_pk_fma_f32 v[92:93], v[30:31], v[94:95], v[100:101]
	v_cvt_pk_bf16_f32 v90, v90, v91
	v_cvt_pk_bf16_f32 v91, v96, v97
	v_lshlrev_b64 v[96:97], 11, v[150:151]
	v_cvt_pk_bf16_f32 v92, v92, v93
	v_cvt_pk_bf16_f32 v93, v104, v105
	v_lshl_add_u64 v[96:97], v[122:123], 0, v[96:97]
	global_store_dwordx4 v[96:97], v[90:93], off
	v_pk_fma_f32 v[96:97], v[2:3], v[102:103], v[34:35]
	v_pk_fma_f32 v[100:101], v[4:5], v[160:161], v[36:37]
	v_pk_fma_f32 v[90:91], v[6:7], v[114:115], v[38:39]
	v_pk_fma_f32 v[92:93], v[8:9], v[116:117], v[40:41]
	v_pk_fma_f32 v[90:91], v[10:11], v[108:109], v[90:91]
	v_pk_fma_f32 v[92:93], v[12:13], v[110:111], v[92:93]
	v_pk_fma_f32 v[100:101], v[16:17], v[112:113], v[100:101]
	v_pk_fma_f32 v[96:97], v[14:15], v[98:99], v[96:97]
	v_pk_fma_f32 v[90:91], v[18:19], v[106:107], v[90:91]
	v_pk_fma_f32 v[92:93], v[20:21], v[152:153], v[92:93]
	v_lshlrev_b32_e32 v102, 16, v86
	v_and_b32_e32 v103, 0xffff0000, v86
	v_lshlrev_b32_e32 v104, 16, v87
	v_and_b32_e32 v105, 0xffff0000, v87
	v_pk_fma_f32 v[96:97], v[22:23], v[94:95], v[96:97]
	v_pk_fma_f32 v[100:101], v[24:25], v[154:155], v[100:101]
	v_pk_fma_f32 v[92:93], v[28:29], v[104:105], v[92:93]
	v_pk_fma_f32 v[86:87], v[26:27], v[102:103], v[90:91]
	v_lshlrev_b32_e32 v90, 16, v88
	v_and_b32_e32 v91, 0xffff0000, v88
	v_lshlrev_b32_e32 v114, 16, v89
	v_and_b32_e32 v115, 0xffff0000, v89
	v_ashrrev_i32_e32 v149, 31, v148
	v_pk_fma_f32 v[100:101], v[32:33], v[114:115], v[100:101]
	v_pk_fma_f32 v[88:89], v[30:31], v[90:91], v[96:97]
	v_cvt_pk_bf16_f32 v86, v86, v87
	v_cvt_pk_bf16_f32 v87, v92, v93
	v_lshlrev_b64 v[92:93], 11, v[148:149]
	v_cvt_pk_bf16_f32 v88, v88, v89
	v_cvt_pk_bf16_f32 v89, v100, v101
	v_lshl_add_u64 v[92:93], v[122:123], 0, v[92:93]
	global_store_dwordx4 v[92:93], v[86:89], off
	v_pk_fma_f32 v[92:93], v[2:3], v[98:99], v[34:35]
	v_pk_fma_f32 v[96:97], v[4:5], v[112:113], v[36:37]
	v_pk_fma_f32 v[86:87], v[6:7], v[108:109], v[38:39]
	v_pk_fma_f32 v[88:89], v[8:9], v[110:111], v[40:41]
	v_pk_fma_f32 v[86:87], v[10:11], v[106:107], v[86:87]
	v_pk_fma_f32 v[88:89], v[12:13], v[152:153], v[88:89]
	v_pk_fma_f32 v[96:97], v[16:17], v[154:155], v[96:97]
	v_pk_fma_f32 v[92:93], v[14:15], v[94:95], v[92:93]
	v_pk_fma_f32 v[86:87], v[18:19], v[102:103], v[86:87]
	v_pk_fma_f32 v[88:89], v[20:21], v[104:105], v[88:89]
	v_lshlrev_b32_e32 v98, 16, v82
	v_and_b32_e32 v99, 0xffff0000, v82
	v_lshlrev_b32_e32 v100, 16, v83
	v_and_b32_e32 v101, 0xffff0000, v83
	v_pk_fma_f32 v[92:93], v[22:23], v[90:91], v[92:93]
	v_pk_fma_f32 v[96:97], v[24:25], v[114:115], v[96:97]
	v_pk_fma_f32 v[88:89], v[28:29], v[100:101], v[88:89]
	v_pk_fma_f32 v[82:83], v[26:27], v[98:99], v[86:87]
	v_lshlrev_b32_e32 v86, 16, v84
	v_and_b32_e32 v87, 0xffff0000, v84
	v_lshlrev_b32_e32 v108, 16, v85
	v_and_b32_e32 v109, 0xffff0000, v85
	v_ashrrev_i32_e32 v147, 31, v146
	v_pk_fma_f32 v[96:97], v[32:33], v[108:109], v[96:97]
	v_pk_fma_f32 v[84:85], v[30:31], v[86:87], v[92:93]
	v_cvt_pk_bf16_f32 v82, v82, v83
	v_cvt_pk_bf16_f32 v83, v88, v89
	v_lshlrev_b64 v[88:89], 11, v[146:147]
	v_cvt_pk_bf16_f32 v84, v84, v85
	v_cvt_pk_bf16_f32 v85, v96, v97
	v_lshl_add_u64 v[88:89], v[122:123], 0, v[88:89]
	global_store_dwordx4 v[88:89], v[82:85], off
	v_pk_fma_f32 v[88:89], v[2:3], v[94:95], v[34:35]
	v_pk_fma_f32 v[92:93], v[4:5], v[154:155], v[36:37]
	v_pk_fma_f32 v[82:83], v[6:7], v[106:107], v[38:39]
	v_pk_fma_f32 v[84:85], v[8:9], v[152:153], v[40:41]
	v_pk_fma_f32 v[82:83], v[10:11], v[102:103], v[82:83]
	v_pk_fma_f32 v[84:85], v[12:13], v[104:105], v[84:85]
	v_pk_fma_f32 v[92:93], v[16:17], v[114:115], v[92:93]
	v_pk_fma_f32 v[88:89], v[14:15], v[90:91], v[88:89]
	v_pk_fma_f32 v[82:83], v[18:19], v[98:99], v[82:83]
	v_pk_fma_f32 v[84:85], v[20:21], v[100:101], v[84:85]
	v_lshlrev_b32_e32 v94, 16, v78
	v_and_b32_e32 v95, 0xffff0000, v78
	v_lshlrev_b32_e32 v96, 16, v79
	v_and_b32_e32 v97, 0xffff0000, v79
	v_pk_fma_f32 v[88:89], v[22:23], v[86:87], v[88:89]
	v_pk_fma_f32 v[92:93], v[24:25], v[108:109], v[92:93]
	v_pk_fma_f32 v[84:85], v[28:29], v[96:97], v[84:85]
	v_pk_fma_f32 v[78:79], v[26:27], v[94:95], v[82:83]
	v_lshlrev_b32_e32 v82, 16, v80
	v_and_b32_e32 v83, 0xffff0000, v80
	v_lshlrev_b32_e32 v106, 16, v81
	v_and_b32_e32 v107, 0xffff0000, v81
	v_ashrrev_i32_e32 v145, 31, v144
	v_pk_fma_f32 v[92:93], v[32:33], v[106:107], v[92:93]
	v_pk_fma_f32 v[80:81], v[30:31], v[82:83], v[88:89]
	v_cvt_pk_bf16_f32 v78, v78, v79
	v_cvt_pk_bf16_f32 v79, v84, v85
	v_lshlrev_b64 v[84:85], 11, v[144:145]
	v_cvt_pk_bf16_f32 v80, v80, v81
	v_cvt_pk_bf16_f32 v81, v92, v93
	v_lshl_add_u64 v[84:85], v[122:123], 0, v[84:85]
	global_store_dwordx4 v[84:85], v[78:81], off
	v_pk_fma_f32 v[84:85], v[2:3], v[90:91], v[34:35]
	v_pk_fma_f32 v[88:89], v[4:5], v[114:115], v[36:37]
	v_pk_fma_f32 v[78:79], v[6:7], v[102:103], v[38:39]
	v_pk_fma_f32 v[80:81], v[8:9], v[104:105], v[40:41]
	v_pk_fma_f32 v[78:79], v[10:11], v[98:99], v[78:79]
	v_pk_fma_f32 v[80:81], v[12:13], v[100:101], v[80:81]
	v_pk_fma_f32 v[88:89], v[16:17], v[108:109], v[88:89]
	v_pk_fma_f32 v[84:85], v[14:15], v[86:87], v[84:85]
	v_pk_fma_f32 v[78:79], v[18:19], v[94:95], v[78:79]
	v_pk_fma_f32 v[80:81], v[20:21], v[96:97], v[80:81]
	v_lshlrev_b32_e32 v90, 16, v74
	v_and_b32_e32 v91, 0xffff0000, v74
	v_lshlrev_b32_e32 v92, 16, v75
	v_and_b32_e32 v93, 0xffff0000, v75
	v_pk_fma_f32 v[84:85], v[22:23], v[82:83], v[84:85]
	v_pk_fma_f32 v[88:89], v[24:25], v[106:107], v[88:89]
	v_pk_fma_f32 v[80:81], v[28:29], v[92:93], v[80:81]
	v_pk_fma_f32 v[74:75], v[26:27], v[90:91], v[78:79]
	v_lshlrev_b32_e32 v78, 16, v76
	v_and_b32_e32 v79, 0xffff0000, v76
	v_lshlrev_b32_e32 v102, 16, v77
	v_and_b32_e32 v103, 0xffff0000, v77
	v_ashrrev_i32_e32 v143, 31, v142
	v_pk_fma_f32 v[88:89], v[32:33], v[102:103], v[88:89]
	v_pk_fma_f32 v[76:77], v[30:31], v[78:79], v[84:85]
	v_cvt_pk_bf16_f32 v74, v74, v75
	v_cvt_pk_bf16_f32 v75, v80, v81
	v_lshlrev_b64 v[80:81], 11, v[142:143]
	v_cvt_pk_bf16_f32 v76, v76, v77
	v_cvt_pk_bf16_f32 v77, v88, v89
	v_lshl_add_u64 v[80:81], v[122:123], 0, v[80:81]
	global_store_dwordx4 v[80:81], v[74:77], off
	v_pk_fma_f32 v[80:81], v[2:3], v[86:87], v[34:35]
	v_pk_fma_f32 v[84:85], v[4:5], v[108:109], v[36:37]
	v_pk_fma_f32 v[74:75], v[6:7], v[98:99], v[38:39]
	v_pk_fma_f32 v[76:77], v[8:9], v[100:101], v[40:41]
	v_pk_fma_f32 v[74:75], v[10:11], v[94:95], v[74:75]
	v_pk_fma_f32 v[76:77], v[12:13], v[96:97], v[76:77]
	v_pk_fma_f32 v[84:85], v[16:17], v[106:107], v[84:85]
	v_pk_fma_f32 v[80:81], v[14:15], v[82:83], v[80:81]
	v_pk_fma_f32 v[74:75], v[18:19], v[90:91], v[74:75]
	v_pk_fma_f32 v[76:77], v[20:21], v[92:93], v[76:77]
	v_lshlrev_b32_e32 v86, 16, v70
	v_and_b32_e32 v87, 0xffff0000, v70
	v_lshlrev_b32_e32 v88, 16, v71
	v_and_b32_e32 v89, 0xffff0000, v71
	v_pk_fma_f32 v[80:81], v[22:23], v[78:79], v[80:81]
	v_pk_fma_f32 v[84:85], v[24:25], v[102:103], v[84:85]
	v_pk_fma_f32 v[76:77], v[28:29], v[88:89], v[76:77]
	v_pk_fma_f32 v[70:71], v[26:27], v[86:87], v[74:75]
	v_lshlrev_b32_e32 v74, 16, v72
	v_and_b32_e32 v75, 0xffff0000, v72
	v_lshlrev_b32_e32 v98, 16, v73
	v_and_b32_e32 v99, 0xffff0000, v73
	v_ashrrev_i32_e32 v141, 31, v140
	v_pk_fma_f32 v[84:85], v[32:33], v[98:99], v[84:85]
	v_pk_fma_f32 v[72:73], v[30:31], v[74:75], v[80:81]
	v_cvt_pk_bf16_f32 v70, v70, v71
	v_cvt_pk_bf16_f32 v71, v76, v77
	v_lshlrev_b64 v[76:77], 11, v[140:141]
	v_cvt_pk_bf16_f32 v72, v72, v73
	v_cvt_pk_bf16_f32 v73, v84, v85
	v_lshl_add_u64 v[76:77], v[122:123], 0, v[76:77]
	global_store_dwordx4 v[76:77], v[70:73], off
	v_pk_fma_f32 v[76:77], v[2:3], v[82:83], v[34:35]
	v_pk_fma_f32 v[80:81], v[4:5], v[106:107], v[36:37]
	v_pk_fma_f32 v[70:71], v[6:7], v[94:95], v[38:39]
	v_pk_fma_f32 v[72:73], v[8:9], v[96:97], v[40:41]
	v_pk_fma_f32 v[70:71], v[10:11], v[90:91], v[70:71]
	v_pk_fma_f32 v[72:73], v[12:13], v[92:93], v[72:73]
	v_pk_fma_f32 v[80:81], v[16:17], v[102:103], v[80:81]
	v_pk_fma_f32 v[76:77], v[14:15], v[78:79], v[76:77]
	v_pk_fma_f32 v[70:71], v[18:19], v[86:87], v[70:71]
	v_pk_fma_f32 v[72:73], v[20:21], v[88:89], v[72:73]
	v_lshlrev_b32_e32 v82, 16, v66
	v_and_b32_e32 v83, 0xffff0000, v66
	v_lshlrev_b32_e32 v84, 16, v67
	v_and_b32_e32 v85, 0xffff0000, v67
	v_pk_fma_f32 v[76:77], v[22:23], v[74:75], v[76:77]
	v_pk_fma_f32 v[80:81], v[24:25], v[98:99], v[80:81]
	v_pk_fma_f32 v[72:73], v[28:29], v[84:85], v[72:73]
	v_pk_fma_f32 v[66:67], v[26:27], v[82:83], v[70:71]
	v_lshlrev_b32_e32 v70, 16, v68
	v_and_b32_e32 v71, 0xffff0000, v68
	v_lshlrev_b32_e32 v94, 16, v69
	v_and_b32_e32 v95, 0xffff0000, v69
	v_ashrrev_i32_e32 v139, 31, v138
	v_pk_fma_f32 v[80:81], v[32:33], v[94:95], v[80:81]
	v_pk_fma_f32 v[68:69], v[30:31], v[70:71], v[76:77]
	v_cvt_pk_bf16_f32 v66, v66, v67
	v_cvt_pk_bf16_f32 v67, v72, v73
	v_lshlrev_b64 v[72:73], 11, v[138:139]
	v_cvt_pk_bf16_f32 v68, v68, v69
	v_cvt_pk_bf16_f32 v69, v80, v81
	v_lshl_add_u64 v[72:73], v[122:123], 0, v[72:73]
	global_store_dwordx4 v[72:73], v[66:69], off
	v_pk_fma_f32 v[72:73], v[2:3], v[78:79], v[34:35]
	v_pk_fma_f32 v[76:77], v[4:5], v[102:103], v[36:37]
	v_pk_fma_f32 v[66:67], v[6:7], v[90:91], v[38:39]
	v_pk_fma_f32 v[68:69], v[8:9], v[92:93], v[40:41]
	v_pk_fma_f32 v[66:67], v[10:11], v[86:87], v[66:67]
	v_pk_fma_f32 v[68:69], v[12:13], v[88:89], v[68:69]
	v_pk_fma_f32 v[76:77], v[16:17], v[98:99], v[76:77]
	v_pk_fma_f32 v[72:73], v[14:15], v[74:75], v[72:73]
	v_pk_fma_f32 v[66:67], v[18:19], v[82:83], v[66:67]
	v_pk_fma_f32 v[68:69], v[20:21], v[84:85], v[68:69]
	v_lshlrev_b32_e32 v78, 16, v62
	v_and_b32_e32 v79, 0xffff0000, v62
	v_lshlrev_b32_e32 v80, 16, v63
	v_and_b32_e32 v81, 0xffff0000, v63
	v_pk_fma_f32 v[72:73], v[22:23], v[70:71], v[72:73]
	v_pk_fma_f32 v[76:77], v[24:25], v[94:95], v[76:77]
	v_pk_fma_f32 v[68:69], v[28:29], v[80:81], v[68:69]
	v_pk_fma_f32 v[62:63], v[26:27], v[78:79], v[66:67]
	v_lshlrev_b32_e32 v66, 16, v64
	v_and_b32_e32 v67, 0xffff0000, v64
	v_lshlrev_b32_e32 v90, 16, v65
	v_and_b32_e32 v91, 0xffff0000, v65
	v_ashrrev_i32_e32 v137, 31, v136
	v_pk_fma_f32 v[76:77], v[32:33], v[90:91], v[76:77]
	v_pk_fma_f32 v[64:65], v[30:31], v[66:67], v[72:73]
	v_cvt_pk_bf16_f32 v62, v62, v63
	v_cvt_pk_bf16_f32 v63, v68, v69
	v_lshlrev_b64 v[68:69], 11, v[136:137]
	v_cvt_pk_bf16_f32 v64, v64, v65
	v_cvt_pk_bf16_f32 v65, v76, v77
	v_lshl_add_u64 v[68:69], v[122:123], 0, v[68:69]
	global_store_dwordx4 v[68:69], v[62:65], off
	v_pk_fma_f32 v[68:69], v[2:3], v[74:75], v[34:35]
	v_pk_fma_f32 v[72:73], v[4:5], v[98:99], v[36:37]
	v_pk_fma_f32 v[62:63], v[6:7], v[86:87], v[38:39]
	v_pk_fma_f32 v[64:65], v[8:9], v[88:89], v[40:41]
	v_pk_fma_f32 v[62:63], v[10:11], v[82:83], v[62:63]
	v_pk_fma_f32 v[64:65], v[12:13], v[84:85], v[64:65]
	v_pk_fma_f32 v[72:73], v[16:17], v[94:95], v[72:73]
	v_pk_fma_f32 v[68:69], v[14:15], v[70:71], v[68:69]
	v_pk_fma_f32 v[62:63], v[18:19], v[78:79], v[62:63]
	v_pk_fma_f32 v[64:65], v[20:21], v[80:81], v[64:65]
	v_lshlrev_b32_e32 v74, 16, v58
	v_and_b32_e32 v75, 0xffff0000, v58
	v_lshlrev_b32_e32 v76, 16, v59
	v_and_b32_e32 v77, 0xffff0000, v59
	v_pk_fma_f32 v[68:69], v[22:23], v[66:67], v[68:69]
	v_pk_fma_f32 v[72:73], v[24:25], v[90:91], v[72:73]
	v_pk_fma_f32 v[64:65], v[28:29], v[76:77], v[64:65]
	v_pk_fma_f32 v[58:59], v[26:27], v[74:75], v[62:63]
	v_lshlrev_b32_e32 v62, 16, v60
	v_and_b32_e32 v63, 0xffff0000, v60
	v_lshlrev_b32_e32 v86, 16, v61
	v_and_b32_e32 v87, 0xffff0000, v61
	v_ashrrev_i32_e32 v135, 31, v134
	v_pk_fma_f32 v[72:73], v[32:33], v[86:87], v[72:73]
	v_pk_fma_f32 v[60:61], v[30:31], v[62:63], v[68:69]
	v_cvt_pk_bf16_f32 v58, v58, v59
	v_cvt_pk_bf16_f32 v59, v64, v65
	v_lshlrev_b64 v[64:65], 11, v[134:135]
	v_cvt_pk_bf16_f32 v60, v60, v61
	v_cvt_pk_bf16_f32 v61, v72, v73
	v_lshl_add_u64 v[64:65], v[122:123], 0, v[64:65]
	global_store_dwordx4 v[64:65], v[58:61], off
	v_pk_fma_f32 v[64:65], v[2:3], v[70:71], v[34:35]
	v_pk_fma_f32 v[68:69], v[4:5], v[94:95], v[36:37]
	v_pk_fma_f32 v[58:59], v[6:7], v[82:83], v[38:39]
	v_pk_fma_f32 v[60:61], v[8:9], v[84:85], v[40:41]
	v_pk_fma_f32 v[58:59], v[10:11], v[78:79], v[58:59]
	v_pk_fma_f32 v[60:61], v[12:13], v[80:81], v[60:61]
	v_pk_fma_f32 v[68:69], v[16:17], v[90:91], v[68:69]
	v_pk_fma_f32 v[64:65], v[14:15], v[66:67], v[64:65]
	v_pk_fma_f32 v[58:59], v[18:19], v[74:75], v[58:59]
	v_pk_fma_f32 v[60:61], v[20:21], v[76:77], v[60:61]
	v_lshlrev_b32_e32 v70, 16, v54
	v_and_b32_e32 v71, 0xffff0000, v54
	v_lshlrev_b32_e32 v72, 16, v55
	v_and_b32_e32 v73, 0xffff0000, v55
	v_pk_fma_f32 v[64:65], v[22:23], v[62:63], v[64:65]
	v_pk_fma_f32 v[68:69], v[24:25], v[86:87], v[68:69]
	v_pk_fma_f32 v[60:61], v[28:29], v[72:73], v[60:61]
	v_pk_fma_f32 v[54:55], v[26:27], v[70:71], v[58:59]
	v_lshlrev_b32_e32 v58, 16, v56
	v_and_b32_e32 v59, 0xffff0000, v56
	v_lshlrev_b32_e32 v82, 16, v57
	v_and_b32_e32 v83, 0xffff0000, v57
	v_ashrrev_i32_e32 v133, 31, v132
	v_pk_fma_f32 v[68:69], v[32:33], v[82:83], v[68:69]
	v_pk_fma_f32 v[56:57], v[30:31], v[58:59], v[64:65]
	v_cvt_pk_bf16_f32 v54, v54, v55
	v_cvt_pk_bf16_f32 v55, v60, v61
	v_lshlrev_b64 v[60:61], 11, v[132:133]
	v_cvt_pk_bf16_f32 v56, v56, v57
	v_cvt_pk_bf16_f32 v57, v68, v69
	v_lshl_add_u64 v[60:61], v[122:123], 0, v[60:61]
	global_store_dwordx4 v[60:61], v[54:57], off
	v_pk_fma_f32 v[60:61], v[2:3], v[66:67], v[34:35]
	v_pk_fma_f32 v[64:65], v[4:5], v[90:91], v[36:37]
	v_pk_fma_f32 v[54:55], v[6:7], v[78:79], v[38:39]
	v_pk_fma_f32 v[56:57], v[8:9], v[80:81], v[40:41]
	v_pk_fma_f32 v[54:55], v[10:11], v[74:75], v[54:55]
	v_pk_fma_f32 v[56:57], v[12:13], v[76:77], v[56:57]
	v_pk_fma_f32 v[64:65], v[16:17], v[86:87], v[64:65]
	v_pk_fma_f32 v[60:61], v[14:15], v[62:63], v[60:61]
	v_pk_fma_f32 v[54:55], v[18:19], v[70:71], v[54:55]
	v_pk_fma_f32 v[56:57], v[20:21], v[72:73], v[56:57]
	v_lshlrev_b32_e32 v66, 16, v50
	v_and_b32_e32 v67, 0xffff0000, v50
	v_lshlrev_b32_e32 v68, 16, v51
	v_and_b32_e32 v69, 0xffff0000, v51
	v_pk_fma_f32 v[60:61], v[22:23], v[58:59], v[60:61]
	v_pk_fma_f32 v[64:65], v[24:25], v[82:83], v[64:65]
	v_pk_fma_f32 v[56:57], v[28:29], v[68:69], v[56:57]
	v_pk_fma_f32 v[50:51], v[26:27], v[66:67], v[54:55]
	v_lshlrev_b32_e32 v54, 16, v52
	v_and_b32_e32 v55, 0xffff0000, v52
	v_lshlrev_b32_e32 v78, 16, v53
	v_and_b32_e32 v79, 0xffff0000, v53
	v_ashrrev_i32_e32 v131, 31, v130
	v_pk_fma_f32 v[64:65], v[32:33], v[78:79], v[64:65]
	v_pk_fma_f32 v[52:53], v[30:31], v[54:55], v[60:61]
	v_cvt_pk_bf16_f32 v50, v50, v51
	v_cvt_pk_bf16_f32 v51, v56, v57
	v_lshlrev_b64 v[56:57], 11, v[130:131]
	v_cvt_pk_bf16_f32 v52, v52, v53
	v_cvt_pk_bf16_f32 v53, v64, v65
	v_lshl_add_u64 v[56:57], v[122:123], 0, v[56:57]
	global_store_dwordx4 v[56:57], v[50:53], off
	v_pk_fma_f32 v[56:57], v[2:3], v[62:63], v[34:35]
	v_pk_fma_f32 v[60:61], v[4:5], v[86:87], v[36:37]
	v_pk_fma_f32 v[50:51], v[6:7], v[74:75], v[38:39]
	v_pk_fma_f32 v[52:53], v[8:9], v[76:77], v[40:41]
	v_pk_fma_f32 v[50:51], v[10:11], v[70:71], v[50:51]
	v_pk_fma_f32 v[52:53], v[12:13], v[72:73], v[52:53]
	v_pk_fma_f32 v[60:61], v[16:17], v[82:83], v[60:61]
	v_pk_fma_f32 v[56:57], v[14:15], v[58:59], v[56:57]
	v_pk_fma_f32 v[50:51], v[18:19], v[66:67], v[50:51]
	v_pk_fma_f32 v[52:53], v[20:21], v[68:69], v[52:53]
	v_lshlrev_b32_e32 v62, 16, v46
	v_and_b32_e32 v63, 0xffff0000, v46
	v_lshlrev_b32_e32 v64, 16, v47
	v_and_b32_e32 v65, 0xffff0000, v47
	v_pk_fma_f32 v[56:57], v[22:23], v[54:55], v[56:57]
	v_pk_fma_f32 v[60:61], v[24:25], v[78:79], v[60:61]
	v_pk_fma_f32 v[52:53], v[28:29], v[64:65], v[52:53]
	v_pk_fma_f32 v[46:47], v[26:27], v[62:63], v[50:51]
	v_lshlrev_b32_e32 v50, 16, v48
	v_and_b32_e32 v51, 0xffff0000, v48
	v_lshlrev_b32_e32 v74, 16, v49
	v_and_b32_e32 v75, 0xffff0000, v49
	v_ashrrev_i32_e32 v129, 31, v128
	v_pk_fma_f32 v[60:61], v[32:33], v[74:75], v[60:61]
	v_pk_fma_f32 v[48:49], v[30:31], v[50:51], v[56:57]
	v_cvt_pk_bf16_f32 v46, v46, v47
	v_cvt_pk_bf16_f32 v47, v52, v53
	v_lshlrev_b64 v[52:53], 11, v[128:129]
	v_cvt_pk_bf16_f32 v48, v48, v49
	v_cvt_pk_bf16_f32 v49, v60, v61
	v_lshl_add_u64 v[52:53], v[122:123], 0, v[52:53]
	global_store_dwordx4 v[52:53], v[46:49], off
	v_pk_fma_f32 v[52:53], v[2:3], v[58:59], v[34:35]
	v_pk_fma_f32 v[56:57], v[4:5], v[82:83], v[36:37]
	v_pk_fma_f32 v[46:47], v[6:7], v[70:71], v[38:39]
	v_pk_fma_f32 v[48:49], v[8:9], v[72:73], v[40:41]
	v_pk_fma_f32 v[46:47], v[10:11], v[66:67], v[46:47]
	v_pk_fma_f32 v[48:49], v[12:13], v[68:69], v[48:49]
	v_pk_fma_f32 v[56:57], v[16:17], v[78:79], v[56:57]
	v_pk_fma_f32 v[52:53], v[14:15], v[54:55], v[52:53]
	v_pk_fma_f32 v[46:47], v[18:19], v[62:63], v[46:47]
	v_pk_fma_f32 v[48:49], v[20:21], v[64:65], v[48:49]
	v_lshlrev_b32_e32 v54, 16, v42
	v_and_b32_e32 v55, 0xffff0000, v42
	v_lshlrev_b32_e32 v42, 16, v43
	v_and_b32_e32 v43, 0xffff0000, v43
	v_pk_fma_f32 v[50:51], v[22:23], v[50:51], v[52:53]
	v_pk_fma_f32 v[52:53], v[24:25], v[74:75], v[56:57]
	v_pk_fma_f32 v[48:49], v[28:29], v[42:43], v[48:49]
	v_pk_fma_f32 v[42:43], v[26:27], v[54:55], v[46:47]
	v_lshlrev_b32_e32 v46, 16, v44
	v_and_b32_e32 v47, 0xffff0000, v44
	v_lshlrev_b32_e32 v44, 16, v45
	v_and_b32_e32 v45, 0xffff0000, v45
	v_ashrrev_i32_e32 v127, 31, v126
	v_add_u32_e32 v156, s4, v156
	s_movk_i32 s0, 0xfff
	v_pk_fma_f32 v[52:53], v[32:33], v[44:45], v[52:53]
	v_pk_fma_f32 v[44:45], v[30:31], v[46:47], v[50:51]
	v_lshlrev_b64 v[46:47], 11, v[126:127]
	v_cmp_lt_i32_e32 vcc, s0, v156
	v_cvt_pk_bf16_f32 v42, v42, v43
	v_cvt_pk_bf16_f32 v43, v48, v49
	v_cvt_pk_bf16_f32 v44, v44, v45
	v_cvt_pk_bf16_f32 v45, v52, v53
	v_lshl_add_u64 v[46:47], v[122:123], 0, v[46:47]
	s_or_b64 s[14:15], vcc, s[14:15]
	v_add_u32_e32 v124, s5, v124
	global_store_dwordx4 v[46:47], v[42:45], off
	s_andn2_b64 exec, exec, s[14:15]
	s_cbranch_execz .LBB0_1581
.LBB0_1576:
	v_max_i32_e32 v42, 2, v124
	v_lshlrev_b32_e32 v118, 11, v42
	v_lshl_add_u64 v[42:43], v[120:121], 0, v[118:119]
	v_max_i32_e32 v44, 1, v124
	v_add_co_u32_e32 v42, vcc, 0xfffff000, v42
	v_lshlrev_b32_e32 v118, 11, v44
	s_nop 0
	v_addc_co_u32_e32 v43, vcc, -1, v43, vcc
	v_lshl_add_u64 v[44:45], v[120:121], 0, v[118:119]
	v_add_co_u32_e32 v44, vcc, 0xfffff800, v44
	v_add_u32_e32 v154, 1, v124
	s_nop 0
	v_addc_co_u32_e32 v45, vcc, -1, v45, vcc
	global_load_dwordx4 v[114:117], v[42:43], off
	global_load_dwordx4 v[110:113], v[44:45], off
	v_max_i32_e32 v42, 0, v124
	v_lshlrev_b32_e32 v118, 11, v42
	v_med3_i32 v44, v154, 0, v157
	v_lshl_add_u64 v[42:43], v[120:121], 0, v[118:119]
	v_lshlrev_b32_e32 v118, 11, v44
	v_add_u32_e32 v152, 2, v124
	v_lshl_add_u64 v[44:45], v[120:121], 0, v[118:119]
	global_load_dwordx4 v[106:109], v[42:43], off
	global_load_dwordx4 v[102:105], v[44:45], off
	v_med3_i32 v42, v152, 0, v157
	v_add_u32_e32 v150, 3, v124
	v_lshlrev_b32_e32 v118, 11, v42
	v_med3_i32 v44, v150, 0, v157
	v_lshl_add_u64 v[42:43], v[120:121], 0, v[118:119]
	v_lshlrev_b32_e32 v118, 11, v44
	v_add_u32_e32 v148, 4, v124
	v_lshl_add_u64 v[44:45], v[120:121], 0, v[118:119]
	global_load_dwordx4 v[98:101], v[42:43], off
	global_load_dwordx4 v[94:97], v[44:45], off
	v_med3_i32 v42, v148, 0, v157
	v_add_u32_e32 v146, 5, v124
	v_lshlrev_b32_e32 v118, 11, v42
	v_med3_i32 v44, v146, 0, v157
	v_lshl_add_u64 v[42:43], v[120:121], 0, v[118:119]
	v_lshlrev_b32_e32 v118, 11, v44
	v_add_u32_e32 v144, 6, v124
	v_lshl_add_u64 v[44:45], v[120:121], 0, v[118:119]
	global_load_dwordx4 v[90:93], v[42:43], off
	global_load_dwordx4 v[86:89], v[44:45], off
	v_med3_i32 v42, v144, 0, v157
	v_add_u32_e32 v142, 7, v124
	v_lshlrev_b32_e32 v118, 11, v42
	v_med3_i32 v44, v142, 0, v157
	v_lshl_add_u64 v[42:43], v[120:121], 0, v[118:119]
	v_lshlrev_b32_e32 v118, 11, v44
	v_add_u32_e32 v140, 8, v124
	v_lshl_add_u64 v[44:45], v[120:121], 0, v[118:119]
	global_load_dwordx4 v[82:85], v[42:43], off
	global_load_dwordx4 v[78:81], v[44:45], off
	v_med3_i32 v42, v140, 0, v157
	v_add_u32_e32 v138, 9, v124
	v_lshlrev_b32_e32 v118, 11, v42
	v_med3_i32 v44, v138, 0, v157
	v_lshl_add_u64 v[42:43], v[120:121], 0, v[118:119]
	v_lshlrev_b32_e32 v118, 11, v44
	v_add_u32_e32 v136, 10, v124
	v_lshl_add_u64 v[44:45], v[120:121], 0, v[118:119]
	global_load_dwordx4 v[74:77], v[42:43], off
	global_load_dwordx4 v[70:73], v[44:45], off
	v_med3_i32 v42, v136, 0, v157
	v_add_u32_e32 v134, 11, v124
	v_lshlrev_b32_e32 v118, 11, v42
	v_med3_i32 v44, v134, 0, v157
	v_lshl_add_u64 v[42:43], v[120:121], 0, v[118:119]
	v_lshlrev_b32_e32 v118, 11, v44
	v_add_u32_e32 v132, 12, v124
	v_lshl_add_u64 v[44:45], v[120:121], 0, v[118:119]
	global_load_dwordx4 v[66:69], v[42:43], off
	global_load_dwordx4 v[62:65], v[44:45], off
	v_med3_i32 v42, v132, 0, v157
	v_add_u32_e32 v130, 13, v124
	v_lshlrev_b32_e32 v118, 11, v42
	v_med3_i32 v44, v130, 0, v157
	v_lshl_add_u64 v[42:43], v[120:121], 0, v[118:119]
	v_lshlrev_b32_e32 v118, 11, v44
	v_add_u32_e32 v128, 14, v124
	v_lshl_add_u64 v[44:45], v[120:121], 0, v[118:119]
	global_load_dwordx4 v[58:61], v[42:43], off
	global_load_dwordx4 v[54:57], v[44:45], off
	v_med3_i32 v42, v128, 0, v157
	v_add_u32_e32 v126, 15, v124
	v_lshlrev_b32_e32 v118, 11, v42
	v_med3_i32 v44, v126, 0, v157
	v_lshl_add_u64 v[42:43], v[120:121], 0, v[118:119]
	v_lshlrev_b32_e32 v118, 11, v44
	v_lshl_add_u64 v[44:45], v[120:121], 0, v[118:119]
	global_load_dwordx4 v[50:53], v[42:43], off
	global_load_dwordx4 v[46:49], v[44:45], off
	v_and_b32_e32 v125, 0x7f0, v124
	s_movk_i32 s0, 0x7ef
	v_cmp_lt_i32_e32 vcc, s0, v125
	s_and_saveexec_b64 s[0:1], vcc
	s_xor_b64 s[16:17], exec, s[0:1]
	s_or_saveexec_b64 s[16:17], s[16:17]
	v_mov_b32_e32 v42, 0
	v_mov_b32_e32 v43, 0
	v_mov_b32_e32 v44, 0
	v_mov_b32_e32 v45, 0
	s_xor_b64 exec, exec, s[16:17]
	s_cbranch_execz .LBB0_1575
	v_max_i32_e32 v42, -16, v124
	v_add_u32_e32 v42, 16, v42
	v_min_u32_e32 v42, 0xffff, v42
	v_lshlrev_b32_e32 v118, 11, v42
	v_lshl_add_u64 v[42:43], v[120:121], 0, v[118:119]
	global_load_dwordx4 v[42:45], v[42:43], off
	v_cmp_eq_u32_e32 vcc, 0, v125
	s_and_saveexec_b64 s[18:19], vcc
	s_cbranch_execz .LBB0_1574
	s_waitcnt vmcnt(0) lgkmcnt(0)
	v_mov_b32_e32 v117, 0
	v_mov_b32_e32 v116, v117
	v_mov_b32_e32 v115, v117
	v_mov_b32_e32 v114, v117
	v_mov_b32_e32 v113, v117
	v_mov_b32_e32 v112, v117
	v_mov_b32_e32 v111, v117
	v_mov_b32_e32 v110, v117
	s_branch .LBB0_1574

.LBB0_1645:
	s_add_u32 s57, s48, s56
	s_addc_u32 s58, s49, 0
	s_add_u32 s59, s57, 0x100
	s_addc_u32 s60, s58, 0
	s_and_b64 s[0:1], s[54:55], exec
	s_cselect_b32 s61, s43, s60
	s_cselect_b32 s60, s83, s59
	s_add_u32 s0, s14, s56
	s_addc_u32 s1, s15, 0
	s_add_u32 s56, s0, 0x100
	s_addc_u32 s59, s1, 0
	s_and_b64 s[0:1], s[54:55], exec
	s_cselect_b32 s63, s41, s59
	s_cselect_b32 s62, s94, s56
	s_add_u32 s64, s57, 0x40080
	s_addc_u32 s65, s58, 0
	s_add_i32 s0, s85, s37
	s_add_i32 m0, s39, 0xc000
	s_add_i32 s71, s39, 0xe000
	s_add_i32 s70, s0, 0x2000
	s_add_u32 s58, s62, 0x10000
	s_addc_u32 s59, s63, 0
	s_add_i32 s1, s4, s37
	ds_read_b128 v[26:29], v225
	ds_read_b128 v[30:33], v225 offset:1024
	ds_read_b128 v[42:45], v225 offset:2048
	ds_read_b128 v[46:49], v225 offset:3072
	s_add_i32 s96, s1, 0x2000
	s_add_i32 s81, 0, 0x18000
	s_add_u32 s56, s60, 0x40000
	s_addc_u32 s57, s61, 0
	s_add_i32 s78, s81, s37
	s_add_i32 s79, 0, 0x1c000
	s_add_i32 s80, s78, 0x2000
	s_add_u32 s54, s62, 0x10080
	s_addc_u32 s55, s63, 0
	s_add_i32 vcc_hi, s79, s37
	s_add_i32 vcc_lo, vcc_hi, 0x2000
	v_lshl_add_u64 v[190:191], s[64:65], 0, v[160:161]
	ds_read_b128 v[146:149], v226
	ds_read_b128 v[150:153], v226 offset:1024
	ds_read_b128 v[166:169], v226 offset:2048
	ds_read_b128 v[170:173], v226 offset:3072
	ds_read_b128 v[174:177], v226 offset:4096
	ds_read_b128 v[178:181], v226 offset:5120
	ds_read_b128 v[182:185], v226 offset:6144
	ds_read_b128 v[186:189], v226 offset:7168
	global_load_lds_dwordx4 v[190:191], off
	v_lshl_add_u64 v[190:191], s[64:65], 0, v[156:157]
	s_mov_b32 m0, s71
	s_nop 0
	global_load_lds_dwordx4 v[190:191], off
	s_waitcnt lgkmcnt(8)
	s_waitcnt vmcnt(10)
	s_barrier
	s_waitcnt lgkmcnt(0)
	s_waitcnt lgkmcnt(0)
	v_mfma_f32_16x16x32_bf16 v[142:145], v[26:29], v[146:149], v[142:145]
	v_mfma_f32_16x16x32_bf16 v[134:137], v[42:45], v[146:149], v[134:137]
	v_mfma_f32_16x16x32_bf16 v[126:129], v[26:29], v[166:169], v[126:129]
	v_mfma_f32_16x16x32_bf16 v[118:121], v[42:45], v[166:169], v[118:121]
	v_mfma_f32_16x16x32_bf16 v[110:113], v[26:29], v[174:177], v[110:113]
	v_mfma_f32_16x16x32_bf16 v[102:105], v[42:45], v[174:177], v[102:105]
	v_mfma_f32_16x16x32_bf16 v[94:97], v[26:29], v[182:185], v[94:97]
	v_mfma_f32_16x16x32_bf16 v[86:89], v[42:45], v[182:185], v[86:89]
	v_mfma_f32_16x16x32_bf16 v[142:145], v[30:33], v[150:153], v[142:145]
	v_mfma_f32_16x16x32_bf16 v[134:137], v[46:49], v[150:153], v[134:137]
	v_mfma_f32_16x16x32_bf16 v[126:129], v[30:33], v[170:173], v[126:129]
	v_mfma_f32_16x16x32_bf16 v[118:121], v[46:49], v[170:173], v[118:121]
	v_mfma_f32_16x16x32_bf16 v[110:113], v[30:33], v[178:181], v[110:113]
	v_mfma_f32_16x16x32_bf16 v[102:105], v[46:49], v[178:181], v[102:105]
	v_mfma_f32_16x16x32_bf16 v[94:97], v[30:33], v[186:189], v[94:97]
	v_mfma_f32_16x16x32_bf16 v[86:89], v[46:49], v[186:189], v[86:89]
	s_barrier
	s_mov_b32 m0, s0
	v_lshl_add_u64 v[206:207], s[62:63], 0, v[158:159]
	ds_read_b128 v[190:193], v227
	ds_read_b128 v[194:197], v227 offset:1024
	ds_read_b128 v[198:201], v227 offset:2048
	ds_read_b128 v[202:205], v227 offset:3072
	global_load_lds_dwordx4 v[206:207], off
	v_lshl_add_u64 v[208:209], s[62:63], 0, v[154:155]
	s_mov_b32 m0, s70
	s_nop 0
	global_load_lds_dwordx4 v[208:209], off
	s_waitcnt vmcnt(10)
	s_barrier
	s_waitcnt lgkmcnt(0)
	s_waitcnt lgkmcnt(0)
	v_mfma_f32_16x16x32_bf16 v[138:141], v[190:193], v[146:149], v[138:141]
	v_mfma_f32_16x16x32_bf16 v[130:133], v[198:201], v[146:149], v[130:133]
	v_mfma_f32_16x16x32_bf16 v[122:125], v[190:193], v[166:169], v[122:125]
	v_mfma_f32_16x16x32_bf16 v[114:117], v[198:201], v[166:169], v[114:117]
	v_mfma_f32_16x16x32_bf16 v[106:109], v[190:193], v[174:177], v[106:109]
	v_mfma_f32_16x16x32_bf16 v[98:101], v[198:201], v[174:177], v[98:101]
	v_mfma_f32_16x16x32_bf16 v[90:93], v[190:193], v[182:185], v[90:93]
	v_mfma_f32_16x16x32_bf16 v[82:85], v[198:201], v[182:185], v[82:85]
	v_mfma_f32_16x16x32_bf16 v[138:141], v[194:197], v[150:153], v[138:141]
	v_mfma_f32_16x16x32_bf16 v[130:133], v[202:205], v[150:153], v[130:133]
	v_mfma_f32_16x16x32_bf16 v[122:125], v[194:197], v[170:173], v[122:125]
	v_mfma_f32_16x16x32_bf16 v[114:117], v[202:205], v[170:173], v[114:117]
	v_mfma_f32_16x16x32_bf16 v[106:109], v[194:197], v[178:181], v[106:109]
	v_mfma_f32_16x16x32_bf16 v[98:101], v[202:205], v[178:181], v[98:101]
	v_mfma_f32_16x16x32_bf16 v[90:93], v[194:197], v[186:189], v[90:93]
	v_mfma_f32_16x16x32_bf16 v[82:85], v[202:205], v[186:189], v[82:85]
	s_mov_b32 m0, s39
	v_lshl_add_u64 v[210:211], s[60:61], 0, v[160:161]
	s_barrier
	ds_read_b128 v[146:149], v226 offset:16384
	ds_read_b128 v[150:153], v226 offset:17408
	ds_read_b128 v[166:169], v226 offset:18432
	ds_read_b128 v[170:173], v226 offset:19456
	ds_read_b128 v[174:177], v226 offset:20480
	ds_read_b128 v[178:181], v226 offset:21504
	ds_read_b128 v[182:185], v226 offset:22528
	ds_read_b128 v[186:189], v226 offset:23552
	global_load_lds_dwordx4 v[210:211], off
	v_lshl_add_u64 v[212:213], s[60:61], 0, v[156:157]
	s_mov_b32 m0, s53
	s_nop 0
	global_load_lds_dwordx4 v[212:213], off
	s_waitcnt vmcnt(10)
	s_barrier
	s_waitcnt lgkmcnt(0)
	s_waitcnt lgkmcnt(0)
	v_mfma_f32_16x16x32_bf16 v[78:81], v[26:29], v[146:149], v[78:81]
	v_mfma_f32_16x16x32_bf16 v[70:73], v[42:45], v[146:149], v[70:73]
	v_mfma_f32_16x16x32_bf16 v[62:65], v[26:29], v[166:169], v[62:65]
	v_mfma_f32_16x16x32_bf16 v[54:57], v[42:45], v[166:169], v[54:57]
	v_mfma_f32_16x16x32_bf16 v[38:41], v[26:29], v[174:177], v[38:41]
	v_mfma_f32_16x16x32_bf16 v[22:25], v[42:45], v[174:177], v[22:25]
	v_mfma_f32_16x16x32_bf16 v[14:17], v[26:29], v[182:185], v[14:17]
	v_mfma_f32_16x16x32_bf16 v[6:9], v[42:45], v[182:185], v[6:9]
	v_mfma_f32_16x16x32_bf16 v[78:81], v[30:33], v[150:153], v[78:81]
	v_mfma_f32_16x16x32_bf16 v[70:73], v[46:49], v[150:153], v[70:73]
	v_mfma_f32_16x16x32_bf16 v[62:65], v[30:33], v[170:173], v[62:65]
	v_mfma_f32_16x16x32_bf16 v[54:57], v[46:49], v[170:173], v[54:57]
	v_mfma_f32_16x16x32_bf16 v[38:41], v[30:33], v[178:181], v[38:41]
	v_mfma_f32_16x16x32_bf16 v[22:25], v[46:49], v[178:181], v[22:25]
	v_mfma_f32_16x16x32_bf16 v[14:17], v[30:33], v[186:189], v[14:17]
	v_mfma_f32_16x16x32_bf16 v[6:9], v[46:49], v[186:189], v[6:9]
	s_barrier
	s_mov_b32 m0, s1
	v_lshl_add_u64 v[26:27], s[58:59], 0, v[158:159]
	global_load_lds_dwordx4 v[26:27], off
	v_lshl_add_u64 v[26:27], s[58:59], 0, v[154:155]
	s_mov_b32 m0, s96
	s_nop 0
	global_load_lds_dwordx4 v[26:27], off
	s_waitcnt vmcnt(10)
	s_barrier
	v_mfma_f32_16x16x32_bf16 v[34:37], v[190:193], v[174:177], v[34:37]
	v_mfma_f32_16x16x32_bf16 v[18:21], v[198:201], v[174:177], v[18:21]
	v_mfma_f32_16x16x32_bf16 v[10:13], v[190:193], v[182:185], v[10:13]
	v_mfma_f32_16x16x32_bf16 v[2:5], v[198:201], v[182:185], v[2:5]
	v_mfma_f32_16x16x32_bf16 v[26:29], v[190:193], v[146:149], v[74:77]
	v_mfma_f32_16x16x32_bf16 v[30:33], v[198:201], v[146:149], v[66:69]
	v_mfma_f32_16x16x32_bf16 v[42:45], v[190:193], v[166:169], v[58:61]
	v_mfma_f32_16x16x32_bf16 v[46:49], v[198:201], v[166:169], v[50:53]
	v_mfma_f32_16x16x32_bf16 v[34:37], v[194:197], v[178:181], v[34:37]
	v_mfma_f32_16x16x32_bf16 v[18:21], v[202:205], v[178:181], v[18:21]
	v_mfma_f32_16x16x32_bf16 v[10:13], v[194:197], v[186:189], v[10:13]
	v_mfma_f32_16x16x32_bf16 v[2:5], v[202:205], v[186:189], v[2:5]
	v_mfma_f32_16x16x32_bf16 v[26:29], v[194:197], v[150:153], v[26:29]
	v_mfma_f32_16x16x32_bf16 v[30:33], v[202:205], v[150:153], v[30:33]
	v_mfma_f32_16x16x32_bf16 v[42:45], v[194:197], v[170:173], v[42:45]
	v_mfma_f32_16x16x32_bf16 v[46:49], v[202:205], v[170:173], v[46:49]
	v_add_u32_e32 v74, s81, v224
	s_barrier
	ds_read_b128 v[50:53], v74
	ds_read_b128 v[58:61], v74 offset:1024
	ds_read_b128 v[66:69], v74 offset:2048
	ds_read_b128 v[74:77], v74 offset:3072
	s_mov_b32 m0, s66
	v_lshl_add_u64 v[190:191], s[56:57], 0, v[160:161]
	ds_read_b128 v[146:149], v226 offset:32768
	ds_read_b128 v[150:153], v226 offset:33792
	ds_read_b128 v[166:169], v226 offset:34816
	ds_read_b128 v[170:173], v226 offset:35840
	ds_read_b128 v[174:177], v226 offset:36864
	ds_read_b128 v[178:181], v226 offset:37888
	ds_read_b128 v[182:185], v226 offset:38912
	ds_read_b128 v[186:189], v226 offset:39936
	global_load_lds_dwordx4 v[190:191], off
	v_lshl_add_u64 v[190:191], s[56:57], 0, v[156:157]
	s_mov_b32 m0, s67
	s_nop 0
	global_load_lds_dwordx4 v[190:191], off
	s_waitcnt lgkmcnt(8)
	s_waitcnt vmcnt(10)
	s_barrier
	s_waitcnt lgkmcnt(0)
	s_waitcnt lgkmcnt(0)
	v_mfma_f32_16x16x32_bf16 v[142:145], v[50:53], v[146:149], v[142:145]
	v_mfma_f32_16x16x32_bf16 v[134:137], v[66:69], v[146:149], v[134:137]
	v_mfma_f32_16x16x32_bf16 v[126:129], v[50:53], v[166:169], v[126:129]
	v_mfma_f32_16x16x32_bf16 v[118:121], v[66:69], v[166:169], v[118:121]
	v_mfma_f32_16x16x32_bf16 v[110:113], v[50:53], v[174:177], v[110:113]
	v_mfma_f32_16x16x32_bf16 v[102:105], v[66:69], v[174:177], v[102:105]
	v_mfma_f32_16x16x32_bf16 v[94:97], v[50:53], v[182:185], v[94:97]
	v_mfma_f32_16x16x32_bf16 v[86:89], v[66:69], v[182:185], v[86:89]
	v_mfma_f32_16x16x32_bf16 v[142:145], v[58:61], v[150:153], v[142:145]
	v_mfma_f32_16x16x32_bf16 v[134:137], v[74:77], v[150:153], v[134:137]
	v_mfma_f32_16x16x32_bf16 v[126:129], v[58:61], v[170:173], v[126:129]
	v_mfma_f32_16x16x32_bf16 v[118:121], v[74:77], v[170:173], v[118:121]
	v_mfma_f32_16x16x32_bf16 v[110:113], v[58:61], v[178:181], v[110:113]
	v_mfma_f32_16x16x32_bf16 v[102:105], v[74:77], v[178:181], v[102:105]
	v_mfma_f32_16x16x32_bf16 v[94:97], v[58:61], v[186:189], v[94:97]
	v_mfma_f32_16x16x32_bf16 v[86:89], v[74:77], v[186:189], v[86:89]
	s_barrier
	s_mov_b32 m0, s78
	v_add_u32_e32 v202, s79, v224
	v_lshl_add_u64 v[206:207], v[206:207], 0, s[26:27]
	ds_read_b128 v[190:193], v202
	ds_read_b128 v[194:197], v202 offset:1024
	ds_read_b128 v[198:201], v202 offset:2048
	ds_read_b128 v[202:205], v202 offset:3072
	global_load_lds_dwordx4 v[206:207], off
	v_lshl_add_u64 v[206:207], v[208:209], 0, s[26:27]
	s_mov_b32 m0, s80
	s_nop 0
	global_load_lds_dwordx4 v[206:207], off
	s_waitcnt vmcnt(10)
	s_barrier
	s_waitcnt lgkmcnt(0)
	s_waitcnt lgkmcnt(0)
	v_mfma_f32_16x16x32_bf16 v[138:141], v[190:193], v[146:149], v[138:141]
	v_mfma_f32_16x16x32_bf16 v[130:133], v[198:201], v[146:149], v[130:133]
	v_mfma_f32_16x16x32_bf16 v[122:125], v[190:193], v[166:169], v[122:125]
	v_mfma_f32_16x16x32_bf16 v[114:117], v[198:201], v[166:169], v[114:117]
	v_mfma_f32_16x16x32_bf16 v[106:109], v[190:193], v[174:177], v[106:109]
	v_mfma_f32_16x16x32_bf16 v[98:101], v[198:201], v[174:177], v[98:101]
	v_mfma_f32_16x16x32_bf16 v[90:93], v[190:193], v[182:185], v[90:93]
	v_mfma_f32_16x16x32_bf16 v[82:85], v[198:201], v[182:185], v[82:85]
	v_mfma_f32_16x16x32_bf16 v[138:141], v[194:197], v[150:153], v[138:141]
	v_mfma_f32_16x16x32_bf16 v[130:133], v[202:205], v[150:153], v[130:133]
	v_mfma_f32_16x16x32_bf16 v[122:125], v[194:197], v[170:173], v[122:125]
	v_mfma_f32_16x16x32_bf16 v[114:117], v[202:205], v[170:173], v[114:117]
	v_mfma_f32_16x16x32_bf16 v[106:109], v[194:197], v[178:181], v[106:109]
	v_mfma_f32_16x16x32_bf16 v[98:101], v[202:205], v[178:181], v[98:101]
	v_mfma_f32_16x16x32_bf16 v[90:93], v[194:197], v[186:189], v[90:93]
	v_mfma_f32_16x16x32_bf16 v[82:85], v[202:205], v[186:189], v[82:85]
	s_mov_b32 m0, s6
	v_lshl_add_u64 v[206:207], v[210:211], 0, s[26:27]
	s_barrier
	ds_read_b128 v[146:149], v226 offset:49152
	ds_read_b128 v[150:153], v226 offset:50176
	ds_read_b128 v[166:169], v226 offset:51200
	ds_read_b128 v[170:173], v226 offset:52224
	ds_read_b128 v[174:177], v226 offset:53248
	ds_read_b128 v[178:181], v226 offset:54272
	ds_read_b128 v[182:185], v226 offset:55296
	ds_read_b128 v[186:189], v226 offset:56320
	global_load_lds_dwordx4 v[206:207], off
	v_lshl_add_u64 v[206:207], v[212:213], 0, s[26:27]
	s_mov_b32 m0, s7
	s_nop 0
	global_load_lds_dwordx4 v[206:207], off
	s_waitcnt vmcnt(10)
	s_barrier
	s_waitcnt lgkmcnt(0)
	s_waitcnt lgkmcnt(0)
	v_mfma_f32_16x16x32_bf16 v[78:81], v[50:53], v[146:149], v[78:81]
	v_mfma_f32_16x16x32_bf16 v[70:73], v[66:69], v[146:149], v[70:73]
	v_mfma_f32_16x16x32_bf16 v[62:65], v[50:53], v[166:169], v[62:65]
	v_mfma_f32_16x16x32_bf16 v[54:57], v[66:69], v[166:169], v[54:57]
	v_mfma_f32_16x16x32_bf16 v[38:41], v[50:53], v[174:177], v[38:41]
	v_mfma_f32_16x16x32_bf16 v[22:25], v[66:69], v[174:177], v[22:25]
	v_mfma_f32_16x16x32_bf16 v[14:17], v[50:53], v[182:185], v[14:17]
	v_mfma_f32_16x16x32_bf16 v[6:9], v[66:69], v[182:185], v[6:9]
	v_mfma_f32_16x16x32_bf16 v[78:81], v[58:61], v[150:153], v[78:81]
	v_mfma_f32_16x16x32_bf16 v[70:73], v[74:77], v[150:153], v[70:73]
	v_mfma_f32_16x16x32_bf16 v[62:65], v[58:61], v[170:173], v[62:65]
	v_mfma_f32_16x16x32_bf16 v[54:57], v[74:77], v[170:173], v[54:57]
	v_mfma_f32_16x16x32_bf16 v[38:41], v[58:61], v[178:181], v[38:41]
	v_mfma_f32_16x16x32_bf16 v[22:25], v[74:77], v[178:181], v[22:25]
	v_mfma_f32_16x16x32_bf16 v[14:17], v[58:61], v[186:189], v[14:17]
	v_mfma_f32_16x16x32_bf16 v[6:9], v[74:77], v[186:189], v[6:9]
	s_barrier
	s_mov_b32 m0, vcc_hi
	v_lshl_add_u64 v[50:51], s[54:55], 0, v[158:159]
	global_load_lds_dwordx4 v[50:51], off
	v_lshl_add_u64 v[50:51], s[54:55], 0, v[154:155]
	s_mov_b32 m0, vcc_lo
	s_nop 0
	global_load_lds_dwordx4 v[50:51], off
	s_waitcnt vmcnt(10)
	s_barrier
	v_mfma_f32_16x16x32_bf16 v[26:29], v[190:193], v[146:149], v[26:29]
	v_mfma_f32_16x16x32_bf16 v[74:77], v[194:197], v[150:153], v[26:29]
	v_mfma_f32_16x16x32_bf16 v[26:29], v[198:201], v[146:149], v[30:33]
	v_mfma_f32_16x16x32_bf16 v[66:69], v[202:205], v[150:153], v[26:29]
	v_mfma_f32_16x16x32_bf16 v[26:29], v[190:193], v[166:169], v[42:45]
	v_mfma_f32_16x16x32_bf16 v[58:61], v[194:197], v[170:173], v[26:29]
	v_mfma_f32_16x16x32_bf16 v[26:29], v[198:201], v[166:169], v[46:49]
	v_mfma_f32_16x16x32_bf16 v[50:53], v[202:205], v[170:173], v[26:29]
	v_mfma_f32_16x16x32_bf16 v[26:29], v[190:193], v[174:177], v[34:37]
	v_mfma_f32_16x16x32_bf16 v[18:21], v[198:201], v[174:177], v[18:21]
	v_mfma_f32_16x16x32_bf16 v[10:13], v[190:193], v[182:185], v[10:13]
	v_mfma_f32_16x16x32_bf16 v[2:5], v[198:201], v[182:185], v[2:5]
	v_mfma_f32_16x16x32_bf16 v[34:37], v[194:197], v[178:181], v[26:29]
	v_mfma_f32_16x16x32_bf16 v[18:21], v[202:205], v[178:181], v[18:21]
	v_mfma_f32_16x16x32_bf16 v[10:13], v[194:197], v[186:189], v[10:13]
	v_mfma_f32_16x16x32_bf16 v[2:5], v[202:205], v[186:189], v[2:5]
	s_movk_i32 s56, 0x100
	s_andn2_b64 vcc, exec, s[50:51]
	s_mov_b64 s[54:55], -1
	s_mov_b64 s[50:51], 0
	s_barrier
	s_cbranch_vccz .LBB0_1645
	s_lshl_b32 s0, s82, 7
	s_and_b32 s1, s0, 0x380
	v_mov_b32_e32 v167, v222
	v_mov_b32_e32 v26, v223
	s_or_b32 s1, s1, s11
	s_cmp_lt_u32 s82, 8
	v_lshl_add_u32 v166, v26, 3, s1
	s_mov_b32 s1, 0x32100000
	s_cselect_b32 s1, s1, 0x1a100000
	s_cselect_b32 s49, s9, s17
	s_cselect_b32 s48, s8, s16
	s_add_u32 s50, s18, s1
	s_addc_u32 s51, s19, 0
	s_and_b32 s0, s0, 0xfffffc00
	v_add_u32_e32 v26, s0, v166
	s_load_dwordx2 s[0:1], s[20:21], 0x78
	v_ashrrev_i32_e32 v27, 31, v26
	v_readlane_b32 s56, v254, 5
	v_lshlrev_b64 v[146:147], 2, v[26:27]
	v_readlane_b32 s57, v254, 6
	v_readlane_b32 s58, v254, 7
	v_readlane_b32 s59, v254, 8
	s_waitcnt lgkmcnt(0)
	v_lshl_add_u64 v[26:27], s[0:1], 0, v[146:147]
	v_lshl_add_u64 v[42:43], s[56:57], 0, v[146:147]
	v_lshl_add_u64 v[150:151], s[58:59], 0, v[146:147]
	global_load_dwordx4 v[30:33], v[26:27], off offset:16
	global_load_dwordx4 v[46:49], v[26:27], off
	s_nop 0
	global_load_dwordx4 v[26:29], v[42:43], off offset:16
	s_nop 0
	global_load_dwordx4 v[42:45], v[42:43], off
	s_nop 0
	global_load_dwordx4 v[146:149], v[150:151], off offset:16
	s_nop 0
	global_load_dwordx4 v[150:153], v[150:151], off
	s_lshl_b32 s0, s52, 8
	s_add_i32 s0, s0, s10
	s_waitcnt vmcnt(0)
	v_add_f32_e32 v134, v134, v30
	v_add_f32_e32 v142, v142, v46
	v_add_f32_e32 v138, v138, v42
	v_max_f32_e32 v168, v150, v150
	v_mul_f32_e64 v150, |v150|, s5
	v_exp_f32_e32 v232, v150
	v_mul_f32_e32 v138, 0xbfb8aa3b, v138
	v_exp_f32_e32 v138, v138
	v_mul_f32_e32 v142, 0xbfb8aa3b, v142
	v_add_f32_e32 v172, 1.0, v232
	v_add_f32_e32 v150, -1.0, v172
	v_sub_f32_e32 v169, v150, v172
	v_add_f32_e32 v169, 1.0, v169
	v_sub_f32_e32 v150, v232, v150
	v_add_f32_e32 v174, v150, v169
	v_max_f32_e32 v150, v151, v151
	v_min_f32_e32 v169, 0, v150
	v_mul_f32_e64 v150, |v151|, s5
	v_exp_f32_e32 v233, v150
	v_cvt_f64_f32_e32 v[170:171], v172
	v_frexp_exp_i32_f64_e32 v170, v[170:171]
	v_frexp_mant_f32_e32 v173, v172
	v_add_f32_e32 v171, 1.0, v233
	v_add_f32_e32 v150, -1.0, v171
	v_sub_f32_e32 v151, v150, v171
	v_add_f32_e32 v151, 1.0, v151
	v_sub_f32_e32 v150, v233, v150
	v_add_f32_e32 v175, v150, v151
	v_frexp_mant_f32_e32 v176, v171
	v_cvt_f64_f32_e32 v[150:151], v171
	v_cmp_gt_f32_e32 vcc, s72, v173
	v_frexp_exp_i32_f64_e32 v150, v[150:151]
	v_cmp_gt_f32_e64 s[14:15], s72, v176
	v_subbrev_co_u32_e32 v176, vcc, 0, v170, vcc
	s_nop 0
	v_subbrev_co_u32_e64 v173, s[14:15], 0, v150, s[14:15]
	v_sub_u32_e32 v151, 0, v176
	v_ldexp_f32 v150, v172, v151
	v_sub_u32_e32 v172, 0, v173
	v_ldexp_f32 v170, v174, v151
	v_ldexp_f32 v151, v171, v172
	v_ldexp_f32 v171, v175, v172
	v_pk_add_f32 v[174:175], v[150:151], 1.0 op_sel_hi:[1,0]
	v_pk_add_f32 v[184:185], v[150:151], -1.0 op_sel_hi:[1,0]
	v_pk_add_f32 v[178:179], v[174:175], -1.0 op_sel_hi:[1,0]
	v_pk_add_f32 v[186:187], v[184:185], 1.0 op_sel_hi:[1,0]
	v_pk_add_f32 v[178:179], v[150:151], v[178:179] neg_lo:[0,1] neg_hi:[0,1]
	v_pk_add_f32 v[150:151], v[150:151], v[186:187] neg_lo:[0,1] neg_hi:[0,1]
	v_pk_add_f32 v[178:179], v[170:171], v[178:179]
	v_pk_add_f32 v[150:151], v[170:171], v[150:151]
	v_pk_add_f32 v[180:181], v[174:175], v[178:179]
	v_pk_add_f32 v[170:171], v[184:185], v[150:151]
	v_rcp_f32_e32 v182, v180
	v_rcp_f32_e32 v183, v181
	v_pk_add_f32 v[174:175], v[180:181], v[174:175] neg_lo:[0,1] neg_hi:[0,1]
	v_pk_add_f32 v[184:185], v[170:171], v[184:185] neg_lo:[0,1] neg_hi:[0,1]
	v_pk_add_f32 v[174:175], v[178:179], v[174:175] neg_lo:[0,1] neg_hi:[0,1]
	v_pk_mul_f32 v[186:187], v[170:171], v[182:183]
	v_pk_add_f32 v[150:151], v[150:151], v[184:185] neg_lo:[0,1] neg_hi:[0,1]
	v_pk_mul_f32 v[178:179], v[180:181], v[186:187]
	s_mov_b32 s14, 0x3ecc95a3
	v_pk_fma_f32 v[184:185], v[186:187], v[180:181], v[178:179] neg_lo:[0,0,1] neg_hi:[0,0,1]
	v_cvt_f32_i32_e32 v177, v173
	v_pk_fma_f32 v[184:185], v[186:187], v[174:175], v[184:185]
	v_cvt_f32_i32_e32 v176, v176
	v_pk_add_f32 v[188:189], v[178:179], v[184:185]
	v_add_f32_e32 v138, 1.0, v138
	v_pk_add_f32 v[190:191], v[170:171], v[188:189] neg_lo:[0,1] neg_hi:[0,1]
	v_pk_add_f32 v[178:179], v[188:189], v[178:179] neg_lo:[0,1] neg_hi:[0,1]
	v_pk_add_f32 v[170:171], v[170:171], v[190:191] neg_lo:[0,1] neg_hi:[0,1]
	v_rcp_f32_e32 v249, v138
	v_pk_add_f32 v[170:171], v[170:171], v[188:189] neg_lo:[0,1] neg_hi:[0,1]
	v_add_f32_e32 v138, v143, v47
	v_pk_add_f32 v[150:151], v[150:151], v[170:171]
	v_pk_add_f32 v[170:171], v[178:179], v[184:185] neg_lo:[0,1] neg_hi:[0,1]
	v_mul_f32_e32 v138, 0xbfb8aa3b, v138
	v_pk_add_f32 v[150:151], v[170:171], v[150:151]
	v_exp_f32_e32 v138, v138
	v_pk_add_f32 v[170:171], v[190:191], v[150:151]
	v_exp_f32_e32 v142, v142
	v_pk_mul_f32 v[178:179], v[182:183], v[170:171]
	v_pk_add_f32 v[190:191], v[190:191], v[170:171] neg_lo:[0,1] neg_hi:[0,1]
	v_pk_mul_f32 v[184:185], v[180:181], v[178:179]
	v_pk_add_f32 v[150:151], v[150:151], v[190:191]
	v_pk_fma_f32 v[180:181], v[178:179], v[180:181], v[184:185] neg_lo:[0,0,1] neg_hi:[0,0,1]
	v_pk_add_f32 v[196:197], v[186:187], v[178:179]
	v_pk_fma_f32 v[174:175], v[178:179], v[174:175], v[180:181]
	v_add_f32_e32 v138, 1.0, v138
	v_pk_add_f32 v[180:181], v[184:185], v[174:175]
	v_rcp_f32_e32 v143, v138
	v_pk_add_f32 v[192:193], v[170:171], v[180:181] neg_lo:[0,1] neg_hi:[0,1]
	v_pk_add_f32 v[188:189], v[180:181], v[184:185] neg_lo:[0,1] neg_hi:[0,1]
	v_pk_add_f32 v[194:195], v[170:171], v[192:193] neg_lo:[0,1] neg_hi:[0,1]
	v_mov_b32_e32 v170, v181
	v_mov_b32_e32 v184, v185
	v_mov_b32_e32 v185, v193
	v_pk_add_f32 v[194:195], v[194:195], v[180:181] neg_lo:[0,1] neg_hi:[0,1]
	v_pk_add_f32 v[170:171], v[170:171], v[184:185] neg_lo:[0,1] neg_hi:[0,1]
	v_mov_b32_e32 v180, v175
	v_pk_add_f32 v[170:171], v[170:171], v[180:181] neg_lo:[0,1] neg_hi:[0,1]
	v_pk_add_f32 v[188:189], v[188:189], v[174:175] neg_lo:[0,1] neg_hi:[0,1]
	v_mov_b32_e32 v195, v171
	v_pk_add_f32 v[150:151], v[150:151], v[194:195]
	v_mov_b32_e32 v189, v170
	v_pk_add_f32 v[150:151], v[188:189], v[150:151]
	v_pk_add_f32 v[170:171], v[196:197], v[186:187] neg_lo:[0,1] neg_hi:[0,1]
	v_pk_add_f32 v[150:151], v[192:193], v[150:151]
	v_pk_add_f32 v[170:171], v[178:179], v[170:171] neg_lo:[0,1] neg_hi:[0,1]
	v_pk_mul_f32 v[150:151], v[182:183], v[150:151]
	v_pk_mul_f32 v[182:183], v[176:177], s[34:35] op_sel_hi:[1,0]
	v_pk_add_f32 v[150:151], v[170:171], v[150:151]
	v_pk_fma_f32 v[184:185], v[176:177], s[34:35], v[182:183] op_sel_hi:[1,0,1] neg_lo:[0,0,1] neg_hi:[0,0,1]
	v_pk_add_f32 v[174:175], v[196:197], v[150:151]
	v_pk_fma_f32 v[184:185], v[176:177], s[36:37], v[184:185] op_sel_hi:[1,0,1]
	v_pk_add_f32 v[170:171], v[174:175], v[196:197] neg_lo:[0,1] neg_hi:[0,1]
	v_pk_mul_f32 v[178:179], v[174:175], v[174:175]
	v_pk_add_f32 v[170:171], v[150:151], v[170:171] neg_lo:[0,1] neg_hi:[0,1]
	v_mov_b64_e32 v[150:151], s[14:15]
	v_pk_fma_f32 v[180:181], v[178:179], s[28:29], v[150:151] op_sel_hi:[1,0,0]
	v_ldexp_f32 v172, v174, 1
	v_pk_fma_f32 v[180:181], v[178:179], v[180:181], s[30:31] op_sel_hi:[1,1,0]
	v_ldexp_f32 v173, v175, 1
	v_pk_mul_f32 v[174:175], v[174:175], v[178:179]
	v_ldexp_f32 v170, v170, 1
	v_pk_mul_f32 v[174:175], v[174:175], v[180:181]
	v_ldexp_f32 v171, v171, 1
	v_pk_add_f32 v[178:179], v[172:173], v[174:175]
	v_pk_add_f32 v[176:177], v[182:183], v[184:185]
	v_pk_add_f32 v[172:173], v[178:179], v[172:173] neg_lo:[0,1] neg_hi:[0,1]
	v_pk_add_f32 v[182:183], v[176:177], v[182:183] neg_lo:[0,1] neg_hi:[0,1]
	v_pk_add_f32 v[172:173], v[174:175], v[172:173] neg_lo:[0,1] neg_hi:[0,1]
	v_pk_add_f32 v[182:183], v[184:185], v[182:183] neg_lo:[0,1] neg_hi:[0,1]
	v_pk_add_f32 v[170:171], v[170:171], v[172:173]
	v_add_f32_e32 v138, v139, v43
	v_pk_add_f32 v[190:191], v[178:179], v[170:171]
	v_mul_f32_e32 v138, 0xbfb8aa3b, v138
	v_pk_add_f32 v[172:173], v[190:191], v[178:179] neg_lo:[0,1] neg_hi:[0,1]
	v_exp_f32_e32 v138, v138
	v_pk_add_f32 v[170:171], v[170:171], v[172:173] neg_lo:[0,1] neg_hi:[0,1]
	v_add_f32_e32 v142, 1.0, v142
	v_pk_add_f32 v[184:185], v[182:183], v[170:171]
	v_add_f32_e32 v138, 1.0, v138
	v_pk_add_f32 v[172:173], v[184:185], v[182:183] neg_lo:[0,1] neg_hi:[0,1]
	v_rcp_f32_e32 v250, v138
	v_pk_add_f32 v[188:189], v[170:171], v[172:173] neg_lo:[0,1] neg_hi:[0,1]
	v_max_f32_e32 v170, v152, v152
	v_mul_f32_e64 v152, |v152|, s5
	v_exp_f32_e32 v236, v152
	v_pk_add_f32 v[174:175], v[184:185], v[172:173] neg_lo:[0,1] neg_hi:[0,1]
	v_min_f32_e32 v180, 0, v170
	v_pk_add_f32 v[186:187], v[182:183], v[174:175] neg_lo:[0,1] neg_hi:[0,1]
	v_add_f32_e32 v172, 1.0, v236
	v_add_f32_e32 v152, -1.0, v172
	v_sub_f32_e32 v170, v152, v172
	v_add_f32_e32 v170, 1.0, v170
	v_sub_f32_e32 v152, v236, v152
	v_add_f32_e32 v173, v152, v170
	v_max_f32_e32 v152, v153, v153
	v_min_f32_e32 v181, 0, v152
	v_mul_f32_e64 v152, |v153|, s5
	v_exp_f32_e32 v238, v152
	v_cvt_f64_f32_e32 v[170:171], v172
	v_frexp_exp_i32_f64_e32 v170, v[170:171]
	v_frexp_mant_f32_e32 v174, v172
	v_add_f32_e32 v171, 1.0, v238
	v_add_f32_e32 v152, -1.0, v171
	v_sub_f32_e32 v153, v152, v171
	v_add_f32_e32 v153, 1.0, v153
	v_sub_f32_e32 v152, v238, v152
	v_add_f32_e32 v175, v152, v153
	v_frexp_mant_f32_e32 v178, v171
	v_cvt_f64_f32_e32 v[152:153], v171
	v_cmp_gt_f32_e32 vcc, s72, v174
	v_frexp_exp_i32_f64_e32 v152, v[152:153]
	v_cmp_gt_f32_e64 s[14:15], s72, v178
	v_subbrev_co_u32_e32 v207, vcc, 0, v170, vcc
	s_nop 0
	v_subbrev_co_u32_e64 v206, s[14:15], 0, v152, s[14:15]
	v_sub_u32_e32 v153, 0, v207
	v_ldexp_f32 v152, v172, v153
	v_sub_u32_e32 v172, 0, v206
	v_ldexp_f32 v170, v173, v153
	v_ldexp_f32 v153, v171, v172
	v_ldexp_f32 v171, v175, v172
	v_pk_add_f32 v[172:173], v[152:153], 1.0 op_sel_hi:[1,0]
	v_pk_add_f32 v[192:193], v[152:153], -1.0 op_sel_hi:[1,0]
	v_pk_add_f32 v[174:175], v[172:173], -1.0 op_sel_hi:[1,0]
	v_pk_add_f32 v[194:195], v[192:193], 1.0 op_sel_hi:[1,0]
	v_pk_add_f32 v[174:175], v[152:153], v[174:175] neg_lo:[0,1] neg_hi:[0,1]
	v_pk_add_f32 v[152:153], v[152:153], v[194:195] neg_lo:[0,1] neg_hi:[0,1]
	v_pk_add_f32 v[174:175], v[170:171], v[174:175]
	v_pk_add_f32 v[152:153], v[170:171], v[152:153]
	v_pk_add_f32 v[178:179], v[172:173], v[174:175]
	v_pk_add_f32 v[170:171], v[192:193], v[152:153]
	v_rcp_f32_e32 v182, v178
	v_rcp_f32_e32 v183, v179
	v_pk_add_f32 v[172:173], v[178:179], v[172:173] neg_lo:[0,1] neg_hi:[0,1]
	v_pk_add_f32 v[192:193], v[170:171], v[192:193] neg_lo:[0,1] neg_hi:[0,1]
	v_pk_add_f32 v[172:173], v[174:175], v[172:173] neg_lo:[0,1] neg_hi:[0,1]
	v_pk_mul_f32 v[194:195], v[170:171], v[182:183]
	v_pk_add_f32 v[152:153], v[152:153], v[192:193] neg_lo:[0,1] neg_hi:[0,1]
	v_pk_mul_f32 v[174:175], v[178:179], v[194:195]
	v_add_f32_e32 v138, v144, v48
	v_pk_fma_f32 v[192:193], v[194:195], v[178:179], v[174:175] neg_lo:[0,0,1] neg_hi:[0,0,1]
	v_mul_f32_e32 v138, 0xbfb8aa3b, v138
	v_pk_fma_f32 v[192:193], v[194:195], v[172:173], v[192:193]
	v_exp_f32_e32 v138, v138
	v_pk_add_f32 v[196:197], v[174:175], v[192:193]
	v_rcp_f32_e32 v142, v142
	v_pk_add_f32 v[198:199], v[170:171], v[196:197] neg_lo:[0,1] neg_hi:[0,1]
	v_pk_add_f32 v[174:175], v[196:197], v[174:175] neg_lo:[0,1] neg_hi:[0,1]
	v_pk_add_f32 v[170:171], v[170:171], v[198:199] neg_lo:[0,1] neg_hi:[0,1]
	v_add_f32_e32 v138, 1.0, v138
	v_pk_add_f32 v[170:171], v[170:171], v[196:197] neg_lo:[0,1] neg_hi:[0,1]
	v_min_f32_e32 v168, 0, v168
	v_pk_add_f32 v[152:153], v[152:153], v[170:171]
	v_pk_add_f32 v[170:171], v[174:175], v[192:193] neg_lo:[0,1] neg_hi:[0,1]
	v_add_f32_e32 v130, v130, v26
	v_pk_add_f32 v[152:153], v[170:171], v[152:153]
	v_mul_f32_e32 v130, 0xbfb8aa3b, v130
	v_pk_add_f32 v[170:171], v[198:199], v[152:153]
	v_exp_f32_e32 v130, v130
	v_pk_mul_f32 v[174:175], v[182:183], v[170:171]
	v_pk_add_f32 v[198:199], v[198:199], v[170:171] neg_lo:[0,1] neg_hi:[0,1]
	v_pk_mul_f32 v[192:193], v[178:179], v[174:175]
	v_pk_add_f32 v[152:153], v[152:153], v[198:199]
	v_pk_fma_f32 v[178:179], v[174:175], v[178:179], v[192:193] neg_lo:[0,0,1] neg_hi:[0,0,1]
	v_pk_add_f32 v[204:205], v[194:195], v[174:175]
	v_pk_fma_f32 v[172:173], v[174:175], v[172:173], v[178:179]
	v_add_f32_e32 v130, 1.0, v130
	v_pk_add_f32 v[178:179], v[192:193], v[172:173]
	v_mul_f32_e32 v134, 0xbfb8aa3b, v134
	v_pk_add_f32 v[200:201], v[170:171], v[178:179] neg_lo:[0,1] neg_hi:[0,1]
	v_pk_add_f32 v[196:197], v[178:179], v[192:193] neg_lo:[0,1] neg_hi:[0,1]
	v_pk_add_f32 v[202:203], v[170:171], v[200:201] neg_lo:[0,1] neg_hi:[0,1]
	v_mov_b32_e32 v170, v179
	v_mov_b32_e32 v192, v193
	v_mov_b32_e32 v193, v201
	v_pk_add_f32 v[202:203], v[202:203], v[178:179] neg_lo:[0,1] neg_hi:[0,1]
	v_pk_add_f32 v[170:171], v[170:171], v[192:193] neg_lo:[0,1] neg_hi:[0,1]
	v_mov_b32_e32 v178, v173
	v_pk_add_f32 v[170:171], v[170:171], v[178:179] neg_lo:[0,1] neg_hi:[0,1]
	v_pk_add_f32 v[196:197], v[196:197], v[172:173] neg_lo:[0,1] neg_hi:[0,1]
	v_mov_b32_e32 v203, v171
	v_pk_add_f32 v[152:153], v[152:153], v[202:203]
	v_mov_b32_e32 v197, v170
	v_pk_add_f32 v[152:153], v[196:197], v[152:153]
	v_pk_add_f32 v[170:171], v[204:205], v[194:195] neg_lo:[0,1] neg_hi:[0,1]
	v_pk_add_f32 v[152:153], v[200:201], v[152:153]
	v_pk_add_f32 v[170:171], v[174:175], v[170:171] neg_lo:[0,1] neg_hi:[0,1]
	v_pk_mul_f32 v[152:153], v[182:183], v[152:153]
	v_cvt_f32_i32_e32 v183, v206
	v_pk_add_f32 v[152:153], v[170:171], v[152:153]
	v_cvt_f32_i32_e32 v182, v207
	v_pk_add_f32 v[170:171], v[204:205], v[152:153]
	v_exp_f32_e32 v134, v134
	v_pk_mul_f32 v[174:175], v[170:171], v[170:171]
	v_pk_add_f32 v[172:173], v[170:171], v[204:205] neg_lo:[0,1] neg_hi:[0,1]
	v_pk_fma_f32 v[178:179], v[174:175], s[28:29], v[150:151] op_sel_hi:[1,0,0]
	v_pk_add_f32 v[152:153], v[152:153], v[172:173] neg_lo:[0,1] neg_hi:[0,1]
	v_ldexp_f32 v172, v170, 1
	v_pk_fma_f32 v[178:179], v[174:175], v[178:179], s[30:31] op_sel_hi:[1,1,0]
	v_ldexp_f32 v173, v171, 1
	v_pk_mul_f32 v[170:171], v[170:171], v[174:175]
	v_pk_mul_f32 v[192:193], v[182:183], s[34:35] op_sel_hi:[1,0]
	v_pk_mul_f32 v[170:171], v[170:171], v[178:179]
	v_ldexp_f32 v152, v152, 1
	v_pk_add_f32 v[174:175], v[172:173], v[170:171]
	v_pk_fma_f32 v[194:195], v[182:183], s[34:35], v[192:193] op_sel_hi:[1,0,1] neg_lo:[0,0,1] neg_hi:[0,0,1]
	v_pk_add_f32 v[172:173], v[174:175], v[172:173] neg_lo:[0,1] neg_hi:[0,1]
	v_ldexp_f32 v153, v153, 1
	v_pk_add_f32 v[170:171], v[170:171], v[172:173] neg_lo:[0,1] neg_hi:[0,1]
	v_pk_fma_f32 v[182:183], v[182:183], s[36:37], v[194:195] op_sel_hi:[1,0,1]
	v_pk_add_f32 v[152:153], v[152:153], v[170:171]
	v_pk_add_f32 v[202:203], v[192:193], v[182:183]
	v_pk_add_f32 v[210:211], v[174:175], v[152:153]
	v_pk_add_f32 v[192:193], v[202:203], v[192:193] neg_lo:[0,1] neg_hi:[0,1]
	v_pk_add_f32 v[170:171], v[210:211], v[174:175] neg_lo:[0,1] neg_hi:[0,1]
	v_pk_add_f32 v[182:183], v[182:183], v[192:193] neg_lo:[0,1] neg_hi:[0,1]
	v_pk_add_f32 v[152:153], v[152:153], v[170:171] neg_lo:[0,1] neg_hi:[0,1]
	v_add_f32_e32 v134, 1.0, v134
	v_pk_add_f32 v[204:205], v[182:183], v[152:153]
	v_rcp_f32_e32 v134, v134
	v_pk_add_f32 v[170:171], v[204:205], v[182:183] neg_lo:[0,1] neg_hi:[0,1]
	v_add_f32_e32 v126, v126, v46
	v_pk_add_f32 v[208:209], v[152:153], v[170:171] neg_lo:[0,1] neg_hi:[0,1]
	v_max_f32_e32 v152, v146, v146
	v_mul_f32_e64 v146, |v146|, s5
	v_exp_f32_e32 v235, v146
	v_pk_add_f32 v[172:173], v[204:205], v[170:171] neg_lo:[0,1] neg_hi:[0,1]
	v_min_f32_e32 v178, 0, v152
	v_pk_add_f32 v[206:207], v[182:183], v[172:173] neg_lo:[0,1] neg_hi:[0,1]
	v_add_f32_e32 v170, 1.0, v235
	v_add_f32_e32 v146, -1.0, v170
	v_sub_f32_e32 v152, v146, v170
	v_add_f32_e32 v152, 1.0, v152
	v_sub_f32_e32 v146, v235, v146
	v_add_f32_e32 v171, v146, v152
	v_max_f32_e32 v146, v147, v147
	v_min_f32_e32 v179, 0, v146
	v_mul_f32_e64 v146, |v147|, s5
	v_exp_f32_e32 v237, v146
	v_cvt_f64_f32_e32 v[152:153], v170
	v_frexp_exp_i32_f64_e32 v152, v[152:153]
	v_frexp_mant_f32_e32 v172, v170
	v_add_f32_e32 v153, 1.0, v237
	v_add_f32_e32 v146, -1.0, v153
	v_sub_f32_e32 v147, v146, v153
	v_add_f32_e32 v147, 1.0, v147
	v_sub_f32_e32 v146, v237, v146
	v_add_f32_e32 v173, v146, v147
	v_frexp_mant_f32_e32 v174, v153
	v_cvt_f64_f32_e32 v[146:147], v153
	v_cmp_gt_f32_e32 vcc, s72, v172
	v_frexp_exp_i32_f64_e32 v146, v[146:147]
	v_cmp_gt_f32_e64 s[14:15], s72, v174
	v_subbrev_co_u32_e32 v217, vcc, 0, v152, vcc
	s_nop 0
	v_subbrev_co_u32_e64 v216, s[14:15], 0, v146, s[14:15]
	v_sub_u32_e32 v147, 0, v217
	v_ldexp_f32 v146, v170, v147
	v_sub_u32_e32 v170, 0, v216
	v_ldexp_f32 v152, v171, v147
	v_ldexp_f32 v147, v153, v170
	v_ldexp_f32 v153, v173, v170
	v_pk_add_f32 v[170:171], v[146:147], 1.0 op_sel_hi:[1,0]
	v_pk_add_f32 v[192:193], v[146:147], -1.0 op_sel_hi:[1,0]
	v_pk_add_f32 v[172:173], v[170:171], -1.0 op_sel_hi:[1,0]
	v_pk_add_f32 v[194:195], v[192:193], 1.0 op_sel_hi:[1,0]
	v_pk_add_f32 v[172:173], v[146:147], v[172:173] neg_lo:[0,1] neg_hi:[0,1]
	v_pk_add_f32 v[146:147], v[146:147], v[194:195] neg_lo:[0,1] neg_hi:[0,1]
	v_pk_add_f32 v[172:173], v[152:153], v[172:173]
	v_pk_add_f32 v[146:147], v[152:153], v[146:147]
	v_pk_add_f32 v[174:175], v[170:171], v[172:173]
	v_pk_add_f32 v[152:153], v[192:193], v[146:147]
	v_rcp_f32_e32 v182, v174
	v_rcp_f32_e32 v183, v175
	v_pk_add_f32 v[170:171], v[174:175], v[170:171] neg_lo:[0,1] neg_hi:[0,1]
	v_pk_add_f32 v[192:193], v[152:153], v[192:193] neg_lo:[0,1] neg_hi:[0,1]
	v_pk_add_f32 v[170:171], v[172:173], v[170:171] neg_lo:[0,1] neg_hi:[0,1]
	v_pk_mul_f32 v[194:195], v[152:153], v[182:183]
	v_pk_add_f32 v[146:147], v[146:147], v[192:193] neg_lo:[0,1] neg_hi:[0,1]
	v_pk_mul_f32 v[172:173], v[174:175], v[194:195]
	v_mul_f32_e32 v126, 0xbfb8aa3b, v126
	v_pk_fma_f32 v[192:193], v[194:195], v[174:175], v[172:173] neg_lo:[0,0,1] neg_hi:[0,0,1]
	v_exp_f32_e32 v126, v126
	v_pk_fma_f32 v[192:193], v[194:195], v[170:171], v[192:193]
	v_add_f32_e32 v122, v122, v42
	v_pk_add_f32 v[196:197], v[172:173], v[192:193]
	v_add_f32_e32 v126, 1.0, v126
	v_pk_add_f32 v[198:199], v[152:153], v[196:197] neg_lo:[0,1] neg_hi:[0,1]
	v_pk_add_f32 v[172:173], v[196:197], v[172:173] neg_lo:[0,1] neg_hi:[0,1]
	v_pk_add_f32 v[152:153], v[152:153], v[198:199] neg_lo:[0,1] neg_hi:[0,1]
	v_rcp_f32_e32 v126, v126
	v_pk_add_f32 v[152:153], v[152:153], v[196:197] neg_lo:[0,1] neg_hi:[0,1]
	v_mul_f32_e32 v122, 0xbfb8aa3b, v122
	v_pk_add_f32 v[146:147], v[146:147], v[152:153]
	v_pk_add_f32 v[152:153], v[172:173], v[192:193] neg_lo:[0,1] neg_hi:[0,1]
	v_exp_f32_e32 v122, v122
	v_pk_add_f32 v[146:147], v[152:153], v[146:147]
	v_add_f32_e32 v123, v123, v43
	v_pk_add_f32 v[152:153], v[198:199], v[146:147]
	v_add_f32_e32 v122, 1.0, v122
	v_pk_mul_f32 v[172:173], v[182:183], v[152:153]
	v_pk_add_f32 v[198:199], v[198:199], v[152:153] neg_lo:[0,1] neg_hi:[0,1]
	v_pk_mul_f32 v[192:193], v[174:175], v[172:173]
	v_pk_add_f32 v[146:147], v[146:147], v[198:199]
	v_pk_fma_f32 v[174:175], v[172:173], v[174:175], v[192:193] neg_lo:[0,0,1] neg_hi:[0,0,1]
	v_pk_add_f32 v[214:215], v[194:195], v[172:173]
	v_pk_fma_f32 v[170:171], v[172:173], v[170:171], v[174:175]
	v_rcp_f32_e32 v122, v122
	v_pk_add_f32 v[174:175], v[192:193], v[170:171]
	v_mul_f32_e32 v123, 0xbfb8aa3b, v123
	v_pk_add_f32 v[200:201], v[152:153], v[174:175] neg_lo:[0,1] neg_hi:[0,1]
	v_pk_add_f32 v[196:197], v[174:175], v[192:193] neg_lo:[0,1] neg_hi:[0,1]
	v_pk_add_f32 v[212:213], v[152:153], v[200:201] neg_lo:[0,1] neg_hi:[0,1]
	v_mov_b32_e32 v152, v175
	v_mov_b32_e32 v192, v193
	v_mov_b32_e32 v193, v201
	v_pk_add_f32 v[212:213], v[212:213], v[174:175] neg_lo:[0,1] neg_hi:[0,1]
	v_pk_add_f32 v[152:153], v[152:153], v[192:193] neg_lo:[0,1] neg_hi:[0,1]
	v_mov_b32_e32 v174, v171
	v_pk_add_f32 v[152:153], v[152:153], v[174:175] neg_lo:[0,1] neg_hi:[0,1]
	v_pk_add_f32 v[196:197], v[196:197], v[170:171] neg_lo:[0,1] neg_hi:[0,1]
	v_mov_b32_e32 v213, v153
	v_pk_add_f32 v[146:147], v[146:147], v[212:213]
	v_mov_b32_e32 v197, v152
	v_pk_add_f32 v[146:147], v[196:197], v[146:147]
	v_pk_add_f32 v[152:153], v[214:215], v[194:195] neg_lo:[0,1] neg_hi:[0,1]
	v_pk_add_f32 v[146:147], v[200:201], v[146:147]
	v_pk_add_f32 v[152:153], v[172:173], v[152:153] neg_lo:[0,1] neg_hi:[0,1]
	v_pk_mul_f32 v[146:147], v[182:183], v[146:147]
	v_cvt_f32_i32_e32 v183, v216
	v_pk_add_f32 v[146:147], v[152:153], v[146:147]
	v_cvt_f32_i32_e32 v182, v217
	v_pk_add_f32 v[152:153], v[214:215], v[146:147]
	v_exp_f32_e32 v123, v123
	v_pk_mul_f32 v[172:173], v[152:153], v[152:153]
	v_pk_add_f32 v[170:171], v[152:153], v[214:215] neg_lo:[0,1] neg_hi:[0,1]
	v_pk_fma_f32 v[174:175], v[172:173], s[28:29], v[150:151] op_sel_hi:[1,0,0]
	v_pk_add_f32 v[146:147], v[146:147], v[170:171] neg_lo:[0,1] neg_hi:[0,1]
	v_ldexp_f32 v170, v152, 1
	v_pk_fma_f32 v[174:175], v[172:173], v[174:175], s[30:31] op_sel_hi:[1,1,0]
	v_ldexp_f32 v171, v153, 1
	v_pk_mul_f32 v[152:153], v[152:153], v[172:173]
	v_pk_mul_f32 v[194:195], v[182:183], s[34:35] op_sel_hi:[1,0]
	v_pk_mul_f32 v[152:153], v[152:153], v[174:175]
	v_ldexp_f32 v146, v146, 1
	v_pk_add_f32 v[172:173], v[170:171], v[152:153]
	v_pk_fma_f32 v[192:193], v[182:183], s[34:35], v[194:195] op_sel_hi:[1,0,1] neg_lo:[0,0,1] neg_hi:[0,0,1]
	v_pk_add_f32 v[170:171], v[172:173], v[170:171] neg_lo:[0,1] neg_hi:[0,1]
	v_ldexp_f32 v147, v147, 1
	v_pk_add_f32 v[152:153], v[152:153], v[170:171] neg_lo:[0,1] neg_hi:[0,1]
	v_pk_fma_f32 v[182:183], v[182:183], s[36:37], v[192:193] op_sel_hi:[1,0,1]
	v_pk_add_f32 v[146:147], v[146:147], v[152:153]
	v_pk_add_f32 v[192:193], v[194:195], v[182:183]
	v_pk_add_f32 v[200:201], v[172:173], v[146:147]
	v_pk_add_f32 v[194:195], v[192:193], v[194:195] neg_lo:[0,1] neg_hi:[0,1]
	v_pk_add_f32 v[152:153], v[200:201], v[172:173] neg_lo:[0,1] neg_hi:[0,1]
	v_pk_add_f32 v[182:183], v[182:183], v[194:195] neg_lo:[0,1] neg_hi:[0,1]
	v_pk_add_f32 v[146:147], v[146:147], v[152:153] neg_lo:[0,1] neg_hi:[0,1]
	v_add_f32_e32 v123, 1.0, v123
	v_pk_add_f32 v[194:195], v[182:183], v[146:147]
	v_rcp_f32_e32 v123, v123
	v_pk_add_f32 v[152:153], v[194:195], v[182:183] neg_lo:[0,1] neg_hi:[0,1]
	v_add_f32_e32 v124, v124, v44
	v_pk_add_f32 v[170:171], v[194:195], v[152:153] neg_lo:[0,1] neg_hi:[0,1]
	v_pk_add_f32 v[198:199], v[146:147], v[152:153] neg_lo:[0,1] neg_hi:[0,1]
	v_max_f32_e32 v146, v148, v148
	v_pk_add_f32 v[196:197], v[182:183], v[170:171] neg_lo:[0,1] neg_hi:[0,1]
	v_min_f32_e32 v182, 0, v146
	v_mul_f32_e64 v146, |v148|, s5
	v_exp_f32_e32 v239, v146
	v_mul_f32_e32 v124, 0xbfb8aa3b, v124
	v_exp_f32_e32 v124, v124
	v_add_f32_e32 v118, v118, v30
	v_add_f32_e32 v148, 1.0, v239
	v_add_f32_e32 v146, -1.0, v148
	v_sub_f32_e32 v147, v146, v148
	v_add_f32_e32 v147, 1.0, v147
	v_sub_f32_e32 v146, v239, v146
	v_add_f32_e32 v152, v146, v147
	v_cvt_f64_f32_e32 v[146:147], v148
	v_frexp_exp_i32_f64_e32 v170, v[146:147]
	v_max_f32_e32 v146, v149, v149
	v_min_f32_e32 v183, 0, v146
	v_mul_f32_e64 v146, |v149|, s5
	v_exp_f32_e32 v240, v146
	v_frexp_mant_f32_e32 v153, v148
	v_cmp_gt_f32_e32 vcc, s72, v153
	v_add_f32_e32 v124, 1.0, v124
	v_add_f32_e32 v149, 1.0, v240
	v_add_f32_e32 v146, -1.0, v149
	v_sub_f32_e32 v147, v146, v149
	v_add_f32_e32 v147, 1.0, v147
	v_sub_f32_e32 v146, v240, v146
	v_add_f32_e32 v171, v146, v147
	v_frexp_mant_f32_e32 v172, v149
	v_cvt_f64_f32_e32 v[146:147], v149
	v_frexp_exp_i32_f64_e32 v146, v[146:147]
	v_cmp_gt_f32_e64 s[14:15], s72, v172
	v_subbrev_co_u32_e32 v241, vcc, 0, v170, vcc
	s_nop 0
	v_subbrev_co_u32_e64 v234, s[14:15], 0, v146, s[14:15]
	v_sub_u32_e32 v147, 0, v241
	v_ldexp_f32 v146, v148, v147
	v_ldexp_f32 v148, v152, v147
	v_sub_u32_e32 v152, 0, v234
	v_ldexp_f32 v147, v149, v152
	v_ldexp_f32 v149, v171, v152
	v_pk_add_f32 v[152:153], v[146:147], 1.0 op_sel_hi:[1,0]
	v_pk_add_f32 v[212:213], v[146:147], -1.0 op_sel_hi:[1,0]
	v_pk_add_f32 v[170:171], v[152:153], -1.0 op_sel_hi:[1,0]
	v_pk_add_f32 v[214:215], v[212:213], 1.0 op_sel_hi:[1,0]
	v_pk_add_f32 v[170:171], v[146:147], v[170:171] neg_lo:[0,1] neg_hi:[0,1]
	v_pk_add_f32 v[146:147], v[146:147], v[214:215] neg_lo:[0,1] neg_hi:[0,1]
	v_pk_add_f32 v[170:171], v[148:149], v[170:171]
	v_pk_add_f32 v[146:147], v[148:149], v[146:147]
	v_pk_add_f32 v[172:173], v[152:153], v[170:171]
	v_pk_add_f32 v[148:149], v[212:213], v[146:147]
	v_rcp_f32_e32 v174, v172
	v_rcp_f32_e32 v175, v173
	v_pk_add_f32 v[152:153], v[172:173], v[152:153] neg_lo:[0,1] neg_hi:[0,1]
	v_pk_add_f32 v[212:213], v[148:149], v[212:213] neg_lo:[0,1] neg_hi:[0,1]
	v_pk_add_f32 v[152:153], v[170:171], v[152:153] neg_lo:[0,1] neg_hi:[0,1]
	v_pk_mul_f32 v[214:215], v[148:149], v[174:175]
	v_pk_add_f32 v[146:147], v[146:147], v[212:213] neg_lo:[0,1] neg_hi:[0,1]
	v_pk_mul_f32 v[170:171], v[172:173], v[214:215]
	v_cmp_lt_f32_e64 s[14:15], |v233|, s77
	v_pk_fma_f32 v[212:213], v[214:215], v[172:173], v[170:171] neg_lo:[0,0,1] neg_hi:[0,0,1]
	v_rcp_f32_e32 v124, v124
	v_pk_fma_f32 v[212:213], v[214:215], v[152:153], v[212:213]
	v_add_f32_e32 v125, v125, v45
	v_pk_add_f32 v[216:217], v[170:171], v[212:213]
	v_mul_f32_e32 v118, 0xbfb8aa3b, v118
	v_pk_add_f32 v[218:219], v[148:149], v[216:217] neg_lo:[0,1] neg_hi:[0,1]
	v_pk_add_f32 v[170:171], v[216:217], v[170:171] neg_lo:[0,1] neg_hi:[0,1]
	v_pk_add_f32 v[148:149], v[148:149], v[218:219] neg_lo:[0,1] neg_hi:[0,1]
	v_mul_f32_e32 v125, 0xbfb8aa3b, v125
	v_pk_add_f32 v[148:149], v[148:149], v[216:217] neg_lo:[0,1] neg_hi:[0,1]
	v_exp_f32_e32 v118, v118
	v_pk_add_f32 v[146:147], v[146:147], v[148:149]
	v_pk_add_f32 v[148:149], v[170:171], v[212:213] neg_lo:[0,1] neg_hi:[0,1]
	v_exp_f32_e32 v125, v125
	v_pk_add_f32 v[146:147], v[148:149], v[146:147]
	v_add_f32_e32 v118, 1.0, v118
	v_pk_add_f32 v[148:149], v[218:219], v[146:147]
	v_add_f32_e32 v125, 1.0, v125
	v_pk_mul_f32 v[170:171], v[174:175], v[148:149]
	v_pk_add_f32 v[218:219], v[218:219], v[148:149] neg_lo:[0,1] neg_hi:[0,1]
	v_pk_mul_f32 v[212:213], v[172:173], v[170:171]
	v_pk_add_f32 v[146:147], v[146:147], v[218:219]
	v_pk_fma_f32 v[172:173], v[170:171], v[172:173], v[212:213] neg_lo:[0,0,1] neg_hi:[0,0,1]
	v_pk_add_f32 v[244:245], v[214:215], v[170:171]
	v_pk_fma_f32 v[152:153], v[170:171], v[152:153], v[172:173]
	v_rcp_f32_e32 v118, v118
	v_pk_add_f32 v[172:173], v[212:213], v[152:153]
	v_rcp_f32_e32 v125, v125
	v_pk_add_f32 v[220:221], v[148:149], v[172:173] neg_lo:[0,1] neg_hi:[0,1]
	v_pk_add_f32 v[216:217], v[172:173], v[212:213] neg_lo:[0,1] neg_hi:[0,1]
	v_pk_add_f32 v[242:243], v[148:149], v[220:221] neg_lo:[0,1] neg_hi:[0,1]
	v_mov_b32_e32 v148, v173
	v_mov_b32_e32 v212, v213
	v_mov_b32_e32 v213, v221
	v_pk_add_f32 v[242:243], v[242:243], v[172:173] neg_lo:[0,1] neg_hi:[0,1]
	v_pk_add_f32 v[148:149], v[148:149], v[212:213] neg_lo:[0,1] neg_hi:[0,1]
	v_mov_b32_e32 v172, v153
	v_pk_add_f32 v[148:149], v[148:149], v[172:173] neg_lo:[0,1] neg_hi:[0,1]
	v_pk_add_f32 v[216:217], v[216:217], v[152:153] neg_lo:[0,1] neg_hi:[0,1]
	v_mov_b32_e32 v243, v149
	v_pk_add_f32 v[146:147], v[146:147], v[242:243]
	v_mov_b32_e32 v217, v148
	v_pk_add_f32 v[146:147], v[216:217], v[146:147]
	v_pk_add_f32 v[148:149], v[244:245], v[214:215] neg_lo:[0,1] neg_hi:[0,1]
	v_pk_add_f32 v[146:147], v[220:221], v[146:147]
	v_pk_add_f32 v[148:149], v[170:171], v[148:149] neg_lo:[0,1] neg_hi:[0,1]
	v_pk_mul_f32 v[146:147], v[174:175], v[146:147]
	v_cvt_f32_i32_e32 v173, v234
	v_pk_add_f32 v[146:147], v[148:149], v[146:147]
	v_cvt_f32_i32_e32 v172, v241
	v_pk_add_f32 v[148:149], v[244:245], v[146:147]
	v_add_u32_e32 v234, s0, v167
	v_pk_mul_f32 v[170:171], v[148:149], v[148:149]
	v_pk_add_f32 v[152:153], v[148:149], v[244:245] neg_lo:[0,1] neg_hi:[0,1]
	v_pk_fma_f32 v[150:151], v[170:171], s[28:29], v[150:151] op_sel_hi:[1,0,0]
	v_pk_add_f32 v[146:147], v[146:147], v[152:153] neg_lo:[0,1] neg_hi:[0,1]
	v_ldexp_f32 v152, v148, 1
	v_pk_fma_f32 v[150:151], v[170:171], v[150:151], s[30:31] op_sel_hi:[1,1,0]
	v_ldexp_f32 v153, v149, 1
	v_pk_mul_f32 v[148:149], v[148:149], v[170:171]
	v_pk_mul_f32 v[174:175], v[172:173], s[34:35] op_sel_hi:[1,0]
	v_pk_mul_f32 v[148:149], v[148:149], v[150:151]
	v_ldexp_f32 v146, v146, 1
	v_pk_add_f32 v[150:151], v[152:153], v[148:149]
	v_pk_fma_f32 v[212:213], v[172:173], s[34:35], v[174:175] op_sel_hi:[1,0,1] neg_lo:[0,0,1] neg_hi:[0,0,1]
	v_pk_add_f32 v[152:153], v[150:151], v[152:153] neg_lo:[0,1] neg_hi:[0,1]
	v_ldexp_f32 v147, v147, 1
	v_pk_add_f32 v[148:149], v[148:149], v[152:153] neg_lo:[0,1] neg_hi:[0,1]
	v_pk_fma_f32 v[172:173], v[172:173], s[36:37], v[212:213] op_sel_hi:[1,0,1]
	v_pk_add_f32 v[146:147], v[146:147], v[148:149]
	v_pk_add_f32 v[212:213], v[174:175], v[172:173]
	v_pk_add_f32 v[220:221], v[150:151], v[146:147]
	v_pk_add_f32 v[174:175], v[212:213], v[174:175] neg_lo:[0,1] neg_hi:[0,1]
	v_pk_add_f32 v[148:149], v[220:221], v[150:151] neg_lo:[0,1] neg_hi:[0,1]
	v_pk_add_f32 v[172:173], v[172:173], v[174:175] neg_lo:[0,1] neg_hi:[0,1]
	v_pk_add_f32 v[146:147], v[146:147], v[148:149] neg_lo:[0,1] neg_hi:[0,1]
	v_ashrrev_i32_e32 v167, 31, v166
	v_pk_add_f32 v[214:215], v[172:173], v[146:147]
	v_mov_b32_e32 v242, v190
	v_pk_add_f32 v[148:149], v[214:215], v[172:173] neg_lo:[0,1] neg_hi:[0,1]
	v_mov_b32_e32 v243, v176
	v_pk_add_f32 v[218:219], v[146:147], v[148:149] neg_lo:[0,1] neg_hi:[0,1]
	v_mov_b32_e32 v146, v234
	v_pk_add_f32 v[150:151], v[214:215], v[148:149] neg_lo:[0,1] neg_hi:[0,1]
	v_ashrrev_i32_e32 v147, 31, v146
	v_lshlrev_b64 v[146:147], 10, v[146:147]
	v_lshl_add_u64 v[146:147], v[146:147], 0, v[166:167]
	v_lshlrev_b64 v[148:149], 1, v[146:147]
	v_lshl_add_u64 v[174:175], s[24:25], 0, v[148:149]
	v_pk_add_f32 v[216:217], v[172:173], v[150:151] neg_lo:[0,1] neg_hi:[0,1]
	global_load_dwordx4 v[150:153], v[174:175], off
	v_lshl_add_u64 v[170:171], s[50:51], 0, v[146:147]
	v_add_co_u32_e32 v146, vcc, s84, v174
	v_lshl_add_u64 v[172:173], s[48:49], 0, v[148:149]
	s_nop 0
	v_addc_co_u32_e32 v147, vcc, 0, v175, vcc
	global_load_dwordx4 v[146:149], v[146:147], off
	v_cmp_neq_f32_e32 vcc, s73, v232
	v_add_f32_e32 v114, v114, v26
	v_add_f32_e32 v119, v119, v31
	v_mul_f32_e32 v114, 0xbfb8aa3b, v114
	v_mul_f32_e32 v119, 0xbfb8aa3b, v119
	v_exp_f32_e32 v114, v114
	v_exp_f32_e32 v119, v119
	v_add_f32_e32 v120, v120, v32
	v_add_f32_e32 v115, v115, v27
	v_add_f32_e32 v114, 1.0, v114
	v_add_f32_e32 v119, 1.0, v119
	v_rcp_f32_e32 v114, v114
	v_rcp_f32_e32 v119, v119
	v_mul_f32_e32 v120, 0xbfb8aa3b, v120
	v_mul_f32_e32 v115, 0xbfb8aa3b, v115
	v_exp_f32_e32 v120, v120
	v_exp_f32_e32 v115, v115
	v_add_f32_e32 v121, v121, v33
	v_add_f32_e32 v116, v116, v28
	v_add_f32_e32 v120, 1.0, v120
	v_add_f32_e32 v115, 1.0, v115
	v_rcp_f32_e32 v120, v120
	v_rcp_f32_e32 v115, v115
	v_mul_f32_e32 v121, 0xbfb8aa3b, v121
	v_mul_f32_e32 v116, 0xbfb8aa3b, v116
	v_exp_f32_e32 v121, v121
	v_exp_f32_e32 v116, v116
	v_add_f32_e32 v117, v117, v29
	v_mul_f32_e32 v117, 0xbfb8aa3b, v117
	v_add_f32_e32 v121, 1.0, v121
	v_add_f32_e32 v116, 1.0, v116
	v_rcp_f32_e32 v121, v121
	v_rcp_f32_e32 v116, v116
	v_exp_f32_e32 v117, v117
	s_waitcnt vmcnt(0) lgkmcnt(0)
	v_lshlrev_b32_e32 v241, 16, v150
	v_and_b32_e32 v246, 0xffff0000, v150
	v_rcp_f32_e32 v150, v138
	v_add_f32_e32 v138, v140, v44
	v_mul_f32_e32 v138, 0xbfb8aa3b, v138
	v_exp_f32_e32 v138, v138
	v_lshlrev_b32_e32 v247, 16, v151
	v_and_b32_e32 v248, 0xffff0000, v151
	v_add_f32_e32 v117, 1.0, v117
	v_add_f32_e32 v138, 1.0, v138
	v_rcp_f32_e32 v251, v138
	v_add_f32_e32 v138, v145, v49
	v_mul_f32_e32 v138, 0xbfb8aa3b, v138
	v_exp_f32_e32 v138, v138
	v_rcp_f32_e32 v117, v117
	v_add_f32_e32 v138, 1.0, v138
	v_rcp_f32_e32 v151, v138
	v_add_f32_e32 v138, v141, v45
	v_mul_f32_e32 v138, 0xbfb8aa3b, v138
	v_exp_f32_e32 v138, v138
	s_nop 0
	v_add_f32_e32 v138, 1.0, v138
	v_rcp_f32_e32 v252, v138
	v_pk_add_f32 v[138:139], v[176:177], v[190:191]
	s_nop 0
	v_pk_add_f32 v[140:141], v[138:139], v[176:177] neg_lo:[0,1] neg_hi:[0,1]
	v_mov_b32_e32 v176, v191
	v_pk_add_f32 v[144:145], v[138:139], v[140:141] neg_lo:[0,1] neg_hi:[0,1]
	v_mov_b32_e32 v244, v140
	v_mov_b32_e32 v245, v144
	v_mov_b32_e32 v144, v141
	v_pk_add_f32 v[242:243], v[242:243], v[244:245] neg_lo:[0,1] neg_hi:[0,1]
	v_pk_add_f32 v[140:141], v[176:177], v[144:145] neg_lo:[0,1] neg_hi:[0,1]
	v_pk_add_f32 v[242:243], v[242:243], v[242:243] op_sel:[0,1] op_sel_hi:[1,0]
	v_pk_add_f32 v[140:141], v[140:141], v[140:141] op_sel_hi:[0,1]
	v_mov_b32_e32 v243, v185
	v_mov_b32_e32 v185, v141
	v_pk_add_f32 v[140:141], v[242:243], v[184:185]
	v_pk_add_f32 v[176:177], v[188:189], v[186:187]
	v_pk_add_f32 v[144:145], v[138:139], v[140:141]
	s_nop 0
	v_pk_add_f32 v[138:139], v[144:145], v[138:139] neg_lo:[0,1] neg_hi:[0,1]
	s_nop 0
	v_pk_add_f32 v[138:139], v[140:141], v[138:139] neg_lo:[0,1] neg_hi:[0,1]
	s_nop 0
	v_pk_add_f32 v[138:139], v[176:177], v[138:139]
	v_mov_b32_e32 v176, v210
	v_pk_add_f32 v[138:139], v[144:145], v[138:139]
	v_mov_b32_e32 v177, v202
	v_cndmask_b32_e32 v138, v228, v138, vcc
	v_cmp_neq_f32_e32 vcc, s73, v233
	s_nop 1
	v_cndmask_b32_e32 v139, v228, v139, vcc
	v_cmp_ngt_f32_e32 vcc, -1.0, v233
	s_nop 1
	v_cndmask_b32_e32 v139, v229, v139, vcc
	v_cmp_ngt_f32_e32 vcc, -1.0, v232
	s_nop 1
	v_cndmask_b32_e32 v138, v229, v138, vcc
	v_cmp_neq_f32_e32 vcc, -1.0, v232
	s_nop 1
	v_cndmask_b32_e32 v138, v230, v138, vcc
	v_cmp_neq_f32_e32 vcc, -1.0, v233
	s_nop 1
	v_cndmask_b32_e32 v139, v230, v139, vcc
	v_cmp_lt_f32_e64 vcc, |v232|, s77
	v_cndmask_b32_e64 v139, v139, v233, s[14:15]
	v_cmp_lt_f32_e64 s[14:15], |v238|, s77
	v_cndmask_b32_e32 v138, v138, v232, vcc
	v_pk_add_f32 v[138:139], v[168:169], v[138:139] neg_lo:[0,1] neg_hi:[0,1]
	v_cmp_neq_f32_e32 vcc, s73, v236
	v_pk_mul_f32 v[144:145], v[138:139], s[38:39] op_sel_hi:[1,0]
	s_nop 0
	v_pk_mul_f32 v[138:139], v[142:143], v[144:145]
	v_mul_f32_e32 v126, v126, v144
	v_add_f32_e32 v140, v138, v138
	v_mul_f32_e32 v140, 0x3fb8aa3b, v140
	v_exp_f32_e32 v140, v140
	v_cvt_pk_bf16_f32 v138, v138, v139
	v_sub_f32_e32 v140, 1.0, v140
	v_max_f32_e32 v140, 0, v140
	v_sqrt_f32_e32 v140, v140
	s_nop 0
	v_mul_f32_e32 v140, v249, v140
	v_mul_f32_e32 v186, v140, v241
	v_add_f32_e32 v140, v139, v139
	v_mul_f32_e32 v140, 0x3fb8aa3b, v140
	v_exp_f32_e32 v140, v140
	s_nop 0
	v_sub_f32_e32 v140, 1.0, v140
	v_max_f32_e32 v140, 0, v140
	v_sqrt_f32_e32 v140, v140
	s_nop 0
	v_mul_f32_e32 v140, v250, v140
	v_mul_f32_e32 v187, v140, v246
	v_pk_add_f32 v[140:141], v[202:203], v[210:211]
	s_nop 0
	v_pk_add_f32 v[142:143], v[140:141], v[202:203] neg_lo:[0,1] neg_hi:[0,1]
	v_mov_b32_e32 v202, v211
	v_pk_add_f32 v[168:169], v[140:141], v[142:143] neg_lo:[0,1] neg_hi:[0,1]
	v_mov_b32_e32 v184, v142
	v_mov_b32_e32 v185, v168
	v_mov_b32_e32 v168, v143
	v_pk_add_f32 v[176:177], v[176:177], v[184:185] neg_lo:[0,1] neg_hi:[0,1]
	v_pk_add_f32 v[142:143], v[202:203], v[168:169] neg_lo:[0,1] neg_hi:[0,1]
	v_pk_add_f32 v[176:177], v[176:177], v[176:177] op_sel:[0,1] op_sel_hi:[1,0]
	v_pk_add_f32 v[142:143], v[142:143], v[142:143] op_sel_hi:[0,1]
	v_mov_b32_e32 v177, v205
	v_mov_b32_e32 v205, v143
	v_pk_add_f32 v[142:143], v[176:177], v[204:205]
	v_pk_add_f32 v[176:177], v[208:209], v[206:207]
	v_pk_add_f32 v[168:169], v[140:141], v[142:143]
	s_nop 0
	v_pk_add_f32 v[140:141], v[168:169], v[140:141] neg_lo:[0,1] neg_hi:[0,1]
	s_nop 0
	v_pk_add_f32 v[140:141], v[142:143], v[140:141] neg_lo:[0,1] neg_hi:[0,1]
	s_nop 0
	v_pk_add_f32 v[140:141], v[176:177], v[140:141]
	v_rcp_f32_e32 v177, v130
	v_add_f32_e32 v130, v135, v31
	v_pk_add_f32 v[140:141], v[168:169], v[140:141]
	v_mul_f32_e32 v130, 0xbfb8aa3b, v130
	v_cndmask_b32_e32 v139, v228, v140, vcc
	v_cmp_neq_f32_e32 vcc, s73, v238
	v_exp_f32_e32 v130, v130
	v_and_b32_e32 v176, 0xffff0000, v152
	v_cndmask_b32_e32 v140, v228, v141, vcc
	v_cmp_ngt_f32_e32 vcc, -1.0, v238
	v_add_f32_e32 v130, 1.0, v130
	v_rcp_f32_e32 v135, v130
	v_cndmask_b32_e32 v140, v229, v140, vcc
	v_cmp_ngt_f32_e32 vcc, -1.0, v236
	v_add_f32_e32 v130, v131, v27
	v_mul_f32_e32 v130, 0xbfb8aa3b, v130
	v_cndmask_b32_e32 v139, v229, v139, vcc
	v_cmp_neq_f32_e32 vcc, -1.0, v236
	v_exp_f32_e32 v130, v130
	s_nop 0
	v_cndmask_b32_e32 v139, v230, v139, vcc
	v_cmp_neq_f32_e32 vcc, -1.0, v238
	v_add_f32_e32 v130, 1.0, v130
	v_rcp_f32_e32 v184, v130
	v_cndmask_b32_e32 v140, v230, v140, vcc
	v_cmp_lt_f32_e64 vcc, |v236|, s77
	v_cndmask_b32_e64 v141, v140, v238, s[14:15]
	v_add_f32_e32 v130, v136, v32
	v_cndmask_b32_e32 v140, v139, v236, vcc
	v_pk_add_f32 v[140:141], v[180:181], v[140:141] neg_lo:[0,1] neg_hi:[0,1]
	v_mul_f32_e32 v130, 0xbfb8aa3b, v130
	v_pk_mul_f32 v[142:143], v[140:141], s[38:39] op_sel_hi:[1,0]
	v_exp_f32_e32 v130, v130
	v_pk_mul_f32 v[140:141], v[150:151], v[142:143]
	v_lshlrev_b32_e32 v180, 16, v153
	v_add_f32_e32 v139, v140, v140
	v_mul_f32_e32 v139, 0x3fb8aa3b, v139
	v_exp_f32_e32 v139, v139
	v_add_f32_e32 v130, 1.0, v130
	v_rcp_f32_e32 v136, v130
	v_add_f32_e32 v130, v132, v28
	v_sub_f32_e32 v139, 1.0, v139
	v_max_f32_e32 v139, 0, v139
	v_sqrt_f32_e32 v139, v139
	v_mul_f32_e32 v130, 0xbfb8aa3b, v130
	v_exp_f32_e32 v130, v130
	v_and_b32_e32 v181, 0xffff0000, v153
	v_mul_f32_e32 v139, v251, v139
	v_mul_f32_e32 v150, v139, v247
	v_add_f32_e32 v139, v141, v141
	v_mul_f32_e32 v139, 0x3fb8aa3b, v139
	v_exp_f32_e32 v139, v139
	v_add_f32_e32 v130, 1.0, v130
	v_rcp_f32_e32 v185, v130
	v_add_f32_e32 v130, v137, v33
	v_mul_f32_e32 v130, 0xbfb8aa3b, v130
	v_exp_f32_e32 v130, v130
	v_sub_f32_e32 v139, 1.0, v139
	v_max_f32_e32 v139, 0, v139
	v_sqrt_f32_e32 v139, v139
	v_add_f32_e32 v130, 1.0, v130
	v_rcp_f32_e32 v137, v130
	v_add_f32_e32 v130, v133, v29
	v_mul_f32_e32 v130, 0xbfb8aa3b, v130
	v_mul_f32_e32 v139, v252, v139
	v_exp_f32_e32 v130, v130
	v_mul_f32_e32 v151, v139, v248
	v_cvt_pk_bf16_f32 v139, v140, v141
	v_mul_f32_e32 v140, 0x42000000, v186
	v_mul_f32_e32 v141, 0x42000000, v187
	v_mul_f32_e32 v168, 0x42000000, v150
	v_med3_f32 v140, v140, s29, v231
	v_med3_f32 v141, v141, s29, v231
	v_mov_b32_e32 v150, 0
	v_cvt_pk_fp8_f32 v150, v140, v141
	v_add_f32_e32 v130, 1.0, v130
	v_mul_f32_e32 v151, 0x42000000, v151
	v_rcp_f32_e32 v186, v130
	v_pk_add_f32 v[130:131], v[192:193], v[200:201]
	v_med3_f32 v140, v168, s29, v231
	v_med3_f32 v141, v151, s29, v231
	v_pk_add_f32 v[132:133], v[130:131], v[192:193] neg_lo:[0,1] neg_hi:[0,1]
	v_cvt_pk_fp8_f32 v150, v140, v141 op_sel:[0,0,1]
	v_pk_add_f32 v[140:141], v[130:131], v[132:133] neg_lo:[0,1] neg_hi:[0,1]
	v_lshlrev_b32_e32 v151, 16, v152
	v_mov_b32_e32 v152, v200
	v_mov_b32_e32 v153, v192
	v_mov_b32_e32 v168, v132
	v_mov_b32_e32 v169, v140
	v_mov_b32_e32 v192, v201
	v_mov_b32_e32 v140, v133
	v_pk_add_f32 v[152:153], v[152:153], v[168:169] neg_lo:[0,1] neg_hi:[0,1]
	v_pk_add_f32 v[132:133], v[192:193], v[140:141] neg_lo:[0,1] neg_hi:[0,1]
	v_pk_add_f32 v[152:153], v[152:153], v[152:153] op_sel:[0,1] op_sel_hi:[1,0]
	v_pk_add_f32 v[132:133], v[132:133], v[132:133] op_sel_hi:[0,1]
	v_mov_b32_e32 v153, v195
	v_mov_b32_e32 v195, v133
	v_pk_add_f32 v[132:133], v[152:153], v[194:195]
	v_pk_add_f32 v[152:153], v[198:199], v[196:197]
	v_pk_add_f32 v[140:141], v[130:131], v[132:133]
	v_cmp_neq_f32_e32 vcc, s73, v235
	v_pk_add_f32 v[130:131], v[140:141], v[130:131] neg_lo:[0,1] neg_hi:[0,1]
	v_cmp_lt_f32_e64 s[14:15], |v237|, s77
	v_pk_add_f32 v[130:131], v[132:133], v[130:131] neg_lo:[0,1] neg_hi:[0,1]
	v_mov_b32_e32 v168, v220
	v_pk_add_f32 v[130:131], v[152:153], v[130:131]
	v_mov_b32_e32 v169, v212
	v_pk_add_f32 v[130:131], v[140:141], v[130:131]
	s_nop 0
	v_cndmask_b32_e32 v130, v228, v130, vcc
	v_cmp_neq_f32_e32 vcc, s73, v237
	s_nop 1
	v_cndmask_b32_e32 v131, v228, v131, vcc
	v_cmp_ngt_f32_e32 vcc, -1.0, v237
	s_nop 1
	v_cndmask_b32_e32 v131, v229, v131, vcc
	v_cmp_ngt_f32_e32 vcc, -1.0, v235
	s_nop 1
	v_cndmask_b32_e32 v130, v229, v130, vcc
	v_cmp_neq_f32_e32 vcc, -1.0, v235
	s_nop 1
	v_cndmask_b32_e32 v130, v230, v130, vcc
	v_cmp_neq_f32_e32 vcc, -1.0, v237
	s_nop 1
	v_cndmask_b32_e32 v131, v230, v131, vcc
	v_cmp_lt_f32_e64 vcc, |v235|, s77
	v_cndmask_b32_e64 v131, v131, v237, s[14:15]
	v_cmp_lt_f32_e64 s[14:15], |v240|, s77
	v_cndmask_b32_e32 v130, v130, v235, vcc
	v_pk_add_f32 v[130:131], v[178:179], v[130:131] neg_lo:[0,1] neg_hi:[0,1]
	v_cmp_neq_f32_e32 vcc, s73, v239
	v_pk_mul_f32 v[130:131], v[130:131], s[38:39] op_sel_hi:[1,0]
	s_nop 0
	v_pk_mul_f32 v[132:133], v[134:135], v[130:131]
	v_mul_f32_e32 v118, v118, v130
	v_add_f32_e32 v134, v132, v132
	v_mul_f32_e32 v134, 0x3fb8aa3b, v134
	v_exp_f32_e32 v134, v134
	v_cvt_pk_bf16_f32 v140, v132, v133
	v_mul_f32_e32 v119, v119, v131
	v_sub_f32_e32 v134, 1.0, v134
	v_max_f32_e32 v134, 0, v134
	v_sqrt_f32_e32 v134, v134
	s_nop 0
	v_mul_f32_e32 v134, v177, v134
	v_mul_f32_e32 v151, v134, v151
	v_add_f32_e32 v134, v133, v133
	v_mul_f32_e32 v134, 0x3fb8aa3b, v134
	v_exp_f32_e32 v134, v134
	v_pk_add_f32 v[132:133], v[212:213], v[220:221]
	v_sub_f32_e32 v134, 1.0, v134
	v_max_f32_e32 v134, 0, v134
	v_sqrt_f32_e32 v134, v134
	s_nop 0
	v_mul_f32_e32 v134, v184, v134
	v_mul_f32_e32 v178, v134, v176
	v_pk_add_f32 v[134:135], v[132:133], v[212:213] neg_lo:[0,1] neg_hi:[0,1]
	v_mov_b32_e32 v212, v221
	v_pk_add_f32 v[152:153], v[132:133], v[134:135] neg_lo:[0,1] neg_hi:[0,1]
	v_mov_b32_e32 v176, v134
	v_mov_b32_e32 v177, v152
	v_mov_b32_e32 v152, v135
	v_pk_add_f32 v[168:169], v[168:169], v[176:177] neg_lo:[0,1] neg_hi:[0,1]
	v_pk_add_f32 v[134:135], v[212:213], v[152:153] neg_lo:[0,1] neg_hi:[0,1]
	v_pk_add_f32 v[168:169], v[168:169], v[168:169] op_sel:[0,1] op_sel_hi:[1,0]
	v_pk_add_f32 v[134:135], v[134:135], v[134:135] op_sel_hi:[0,1]
	v_mov_b32_e32 v169, v215
	v_mov_b32_e32 v215, v135
	v_pk_add_f32 v[134:135], v[168:169], v[214:215]
	v_pk_add_f32 v[168:169], v[218:219], v[216:217]
	v_pk_add_f32 v[152:153], v[132:133], v[134:135]
	s_nop 0
	v_pk_add_f32 v[132:133], v[152:153], v[132:133] neg_lo:[0,1] neg_hi:[0,1]
	s_nop 0
	v_pk_add_f32 v[132:133], v[134:135], v[132:133] neg_lo:[0,1] neg_hi:[0,1]
	s_nop 0
	v_pk_add_f32 v[132:133], v[168:169], v[132:133]
	s_nop 0
	v_pk_add_f32 v[132:133], v[152:153], v[132:133]
	s_nop 0
	v_cndmask_b32_e32 v132, v228, v132, vcc
	v_cmp_neq_f32_e32 vcc, s73, v240
	s_nop 1
	v_cndmask_b32_e32 v133, v228, v133, vcc
	v_cmp_ngt_f32_e32 vcc, -1.0, v240
	s_nop 1
	v_cndmask_b32_e32 v133, v229, v133, vcc
	v_cmp_ngt_f32_e32 vcc, -1.0, v239
	s_nop 1
	v_cndmask_b32_e32 v132, v229, v132, vcc
	v_cmp_neq_f32_e32 vcc, -1.0, v239
	s_nop 1
	v_cndmask_b32_e32 v132, v230, v132, vcc
	v_cmp_neq_f32_e32 vcc, -1.0, v240
	s_nop 1
	v_cndmask_b32_e32 v133, v230, v133, vcc
	v_cmp_lt_f32_e64 vcc, |v239|, s77
	v_cndmask_b32_e64 v133, v133, v240, s[14:15]
	s_nop 0
	v_cndmask_b32_e32 v132, v132, v239, vcc
	v_pk_add_f32 v[132:133], v[182:183], v[132:133] neg_lo:[0,1] neg_hi:[0,1]
	s_nop 0
	v_pk_mul_f32 v[132:133], v[132:133], s[38:39] op_sel_hi:[1,0]
	s_nop 0
	v_pk_mul_f32 v[134:135], v[136:137], v[132:133]
	v_mul_f32_e32 v120, v120, v132
	v_add_f32_e32 v136, v134, v134
	v_add_f32_e32 v137, v135, v135
	v_mul_f32_e32 v136, 0x3fb8aa3b, v136
	v_mul_f32_e32 v137, 0x3fb8aa3b, v137
	v_exp_f32_e32 v136, v136
	v_exp_f32_e32 v137, v137
	v_cvt_pk_bf16_f32 v141, v134, v135
	v_mul_f32_e32 v134, 0x42000000, v151
	v_sub_f32_e32 v136, 1.0, v136
	v_sub_f32_e32 v137, 1.0, v137
	v_max_f32_e32 v136, 0, v136
	v_max_f32_e32 v137, 0, v137
	v_sqrt_f32_e32 v136, v136
	v_sqrt_f32_e32 v137, v137
	v_mul_f32_e32 v135, 0x42000000, v178
	v_med3_f32 v134, v134, s29, v231
	v_med3_f32 v135, v135, s29, v231
	v_mov_b32_e32 v151, 0
	v_mul_f32_e32 v136, v185, v136
	v_mul_f32_e32 v137, v186, v137
	v_cvt_pk_fp8_f32 v151, v134, v135
	v_mul_f32_e32 v136, v136, v180
	v_mul_f32_e32 v137, v137, v181
	v_mul_f32_e32 v136, 0x42000000, v136
	v_mul_f32_e32 v137, 0x42000000, v137
	v_med3_f32 v134, v136, s29, v231
	v_med3_f32 v135, v137, s29, v231
	v_cvt_pk_fp8_f32 v151, v134, v135 op_sel:[0,0,1]
	global_store_dwordx4 v[172:173], v[138:141], off
	global_store_dwordx2 v[170:171], v[150:151], off
	s_nop 0
	v_add_f32_e32 v138, v126, v126
	v_mul_f32_e32 v138, 0x3fb8aa3b, v138
	v_exp_f32_e32 v138, v138
	v_lshlrev_b32_e32 v134, 16, v146
	v_and_b32_e32 v135, 0xffff0000, v146
	v_lshlrev_b32_e32 v136, 16, v147
	v_sub_f32_e32 v138, 1.0, v138
	v_max_f32_e32 v138, 0, v138
	v_sqrt_f32_e32 v138, v138
	v_and_b32_e32 v137, 0xffff0000, v147
	v_mul_f32_e32 v121, v121, v133
	v_mul_f32_e32 v122, v122, v138
	v_mul_f32_e32 v134, v122, v134
	v_add_f32_e32 v122, v127, v47
	v_mul_f32_e32 v122, 0xbfb8aa3b, v122
	v_exp_f32_e32 v122, v122
	s_nop 0
	v_add_f32_e32 v122, 1.0, v122
	v_rcp_f32_e32 v122, v122
	s_nop 0
	v_mul_f32_e32 v122, v122, v145
	v_add_f32_e32 v127, v122, v122
	v_mul_f32_e32 v127, 0x3fb8aa3b, v127
	v_exp_f32_e32 v127, v127
	v_cvt_pk_bf16_f32 v122, v126, v122
	v_mul_f32_e32 v126, 0x42000000, v134
	v_sub_f32_e32 v127, 1.0, v127
	v_max_f32_e32 v127, 0, v127
	v_sqrt_f32_e32 v127, v127
	s_nop 0
	v_mul_f32_e32 v123, v123, v127
	v_mul_f32_e32 v127, v123, v135
	v_add_f32_e32 v123, v128, v48
	v_mul_f32_e32 v123, 0xbfb8aa3b, v123
	v_exp_f32_e32 v123, v123
	v_mul_f32_e32 v127, 0x42000000, v127
	v_med3_f32 v127, v127, s29, v231
	v_add_f32_e32 v123, 1.0, v123
	v_rcp_f32_e32 v123, v123
	s_nop 0
	v_mul_f32_e32 v123, v123, v142
	v_add_f32_e32 v128, v123, v123
	v_mul_f32_e32 v128, 0x3fb8aa3b, v128
	v_exp_f32_e32 v128, v128
	s_nop 0
	v_sub_f32_e32 v128, 1.0, v128
	v_max_f32_e32 v128, 0, v128
	v_sqrt_f32_e32 v128, v128
	s_nop 0
	v_mul_f32_e32 v124, v124, v128
	v_add_f32_e32 v128, v129, v49
	v_mul_f32_e32 v128, 0xbfb8aa3b, v128
	v_exp_f32_e32 v128, v128
	v_mul_f32_e32 v124, v124, v136
	v_mul_f32_e32 v124, 0x42000000, v124
	v_med3_f32 v124, v124, s29, v231
	v_add_f32_e32 v128, 1.0, v128
	v_rcp_f32_e32 v128, v128
	s_nop 0
	v_mul_f32_e32 v128, v128, v143
	v_add_f32_e32 v129, v128, v128
	v_mul_f32_e32 v129, 0x3fb8aa3b, v129
	v_exp_f32_e32 v129, v129
	v_cvt_pk_bf16_f32 v123, v123, v128
	v_med3_f32 v128, v126, s29, v231
	v_mov_b32_e32 v126, 0
	v_sub_f32_e32 v129, 1.0, v129
	v_max_f32_e32 v129, 0, v129
	v_sqrt_f32_e32 v129, v129
	v_cvt_pk_fp8_f32 v126, v128, v127
	v_lshlrev_b32_e32 v127, 16, v149
	v_and_b32_e32 v128, 0xffff0000, v149
	v_mul_f32_e32 v125, v125, v129
	v_add_f32_e32 v129, v118, v118
	v_mul_f32_e32 v129, 0x3fb8aa3b, v129
	v_exp_f32_e32 v129, v129
	v_mul_f32_e32 v125, v125, v137
	v_mul_f32_e32 v125, 0x42000000, v125
	v_med3_f32 v125, v125, s29, v231
	v_sub_f32_e32 v129, 1.0, v129
	v_max_f32_e32 v129, 0, v129
	v_sqrt_f32_e32 v129, v129
	v_cvt_pk_fp8_f32 v126, v124, v125 op_sel:[0,0,1]
	v_lshlrev_b32_e32 v124, 16, v148
	v_and_b32_e32 v125, 0xffff0000, v148
	v_mul_f32_e32 v114, v114, v129
	v_mul_f32_e32 v114, v114, v124
	v_add_f32_e32 v124, v119, v119
	v_mul_f32_e32 v124, 0x3fb8aa3b, v124
	v_exp_f32_e32 v124, v124
	v_mul_f32_e32 v114, 0x42000000, v114
	v_med3_f32 v114, v114, s29, v231
	v_sub_f32_e32 v124, 1.0, v124
	v_max_f32_e32 v124, 0, v124
	v_sqrt_f32_e32 v124, v124
	s_nop 0
	v_mul_f32_e32 v115, v115, v124
	v_add_f32_e32 v124, v120, v120
	v_mul_f32_e32 v124, 0x3fb8aa3b, v124
	v_exp_f32_e32 v124, v124
	v_mul_f32_e32 v115, v115, v125
	v_mul_f32_e32 v115, 0x42000000, v115
	v_med3_f32 v115, v115, s29, v231
	v_sub_f32_e32 v124, 1.0, v124
	v_max_f32_e32 v124, 0, v124
	v_sqrt_f32_e32 v124, v124
	v_cvt_pk_bf16_f32 v125, v120, v121
	v_mul_f32_e32 v116, v116, v124
	v_add_f32_e32 v124, v121, v121
	v_mul_f32_e32 v124, 0x3fb8aa3b, v124
	v_exp_f32_e32 v124, v124
	v_mul_f32_e32 v116, v116, v127
	v_mov_b32_e32 v127, 0
	v_cvt_pk_fp8_f32 v127, v114, v115
	v_sub_f32_e32 v124, 1.0, v124
	v_max_f32_e32 v124, 0, v124
	v_sqrt_f32_e32 v124, v124
	v_mul_f32_e32 v116, 0x42000000, v116
	v_med3_f32 v114, v116, s29, v231
	v_mul_f32_e32 v117, v117, v124
	v_mul_f32_e32 v117, v117, v128
	v_mul_f32_e32 v117, 0x42000000, v117
	v_med3_f32 v115, v117, s29, v231
	v_cvt_pk_fp8_f32 v127, v114, v115 op_sel:[0,0,1]
	v_add_co_u32_e32 v114, vcc, s84, v172
	v_cvt_pk_bf16_f32 v124, v118, v119
	s_nop 0
	v_addc_co_u32_e32 v115, vcc, 0, v173, vcc
	global_store_dwordx4 v[114:115], v[122:125], off
	v_add_co_u32_e32 v114, vcc, s93, v170
	s_nop 1
	v_addc_co_u32_e32 v115, vcc, 0, v171, vcc
	global_store_dwordx2 v[114:115], v[126:127], off
	v_add_co_u32_e32 v114, vcc, s92, v174
	v_add_f32_e32 v110, v110, v46
	s_nop 0
	v_addc_co_u32_e32 v115, vcc, 0, v175, vcc
	global_load_dwordx4 v[114:117], v[114:115], off
	v_mul_f32_e32 v110, 0xbfb8aa3b, v110
	v_add_f32_e32 v111, v111, v47
	v_exp_f32_e32 v110, v110
	v_mul_f32_e32 v111, 0xbfb8aa3b, v111
	v_exp_f32_e32 v111, v111
	v_add_f32_e32 v112, v112, v48
	v_add_f32_e32 v113, v113, v49
	v_add_f32_e32 v110, 1.0, v110
	v_mul_f32_e32 v112, 0xbfb8aa3b, v112
	v_mul_f32_e32 v113, 0xbfb8aa3b, v113
	v_rcp_f32_e32 v110, v110
	v_exp_f32_e32 v112, v112
	v_exp_f32_e32 v113, v113
	v_add_f32_e32 v111, 1.0, v111
	v_rcp_f32_e32 v111, v111
	v_add_co_u32_e32 v118, vcc, s89, v174
	v_add_f32_e32 v120, v106, v42
	s_nop 0
	v_addc_co_u32_e32 v119, vcc, 0, v175, vcc
	v_add_f32_e32 v122, v108, v44
	v_mul_f32_e32 v110, v110, v144
	v_add_f32_e32 v121, v107, v43
	v_add_f32_e32 v123, v109, v45
	global_load_dwordx4 v[106:109], v[118:119], off
	v_mul_f32_e32 v118, 0xbfb8aa3b, v120
	v_mul_f32_e32 v120, 0xbfb8aa3b, v122
	v_add_f32_e32 v112, 1.0, v112
	v_add_f32_e32 v113, 1.0, v113
	v_add_f32_e32 v122, v110, v110
	v_rcp_f32_e32 v112, v112
	v_rcp_f32_e32 v113, v113
	v_mul_f32_e32 v111, v111, v145
	v_mul_f32_e32 v122, 0x3fb8aa3b, v122
	v_mul_f32_e32 v119, 0xbfb8aa3b, v121
	v_mul_f32_e32 v121, 0xbfb8aa3b, v123
	v_add_f32_e32 v123, v111, v111
	v_exp_f32_e32 v122, v122
	v_exp_f32_e32 v118, v118
	v_mul_f32_e32 v123, 0x3fb8aa3b, v123
	v_exp_f32_e32 v123, v123
	v_exp_f32_e32 v119, v119
	v_mul_f32_e32 v112, v112, v142
	v_mul_f32_e32 v113, v113, v143
	v_add_f32_e32 v124, v112, v112
	v_add_f32_e32 v125, v113, v113
	v_sub_f32_e32 v122, 1.0, v122
	v_add_f32_e32 v118, 1.0, v118
	v_mul_f32_e32 v124, 0x3fb8aa3b, v124
	v_mul_f32_e32 v125, 0x3fb8aa3b, v125
	v_max_f32_e32 v122, 0, v122
	v_rcp_f32_e32 v118, v118
	v_exp_f32_e32 v124, v124
	v_exp_f32_e32 v125, v125
	v_sub_f32_e32 v123, 1.0, v123
	v_sqrt_f32_e32 v122, v122
	v_exp_f32_e32 v120, v120
	v_exp_f32_e32 v121, v121
	v_add_f32_e32 v119, 1.0, v119
	v_max_f32_e32 v123, 0, v123
	v_rcp_f32_e32 v119, v119
	v_sqrt_f32_e32 v123, v123
	v_add_f32_e32 v102, v102, v30
	v_mul_f32_e32 v102, 0xbfb8aa3b, v102
	v_sub_f32_e32 v124, 1.0, v124
	v_sub_f32_e32 v125, 1.0, v125
	v_mul_f32_e32 v118, v118, v122
	v_exp_f32_e32 v102, v102
	v_add_f32_e32 v120, 1.0, v120
	v_add_f32_e32 v121, 1.0, v121
	v_max_f32_e32 v124, 0, v124
	v_rcp_f32_e32 v120, v120
	v_rcp_f32_e32 v121, v121
	v_sqrt_f32_e32 v124, v124
	v_mul_f32_e32 v119, v119, v123
	v_cvt_pk_bf16_f32 v110, v110, v111
	v_cvt_pk_bf16_f32 v111, v112, v113
	v_add_f32_e32 v102, 1.0, v102
	v_rcp_f32_e32 v102, v102
	s_waitcnt vmcnt(0) lgkmcnt(0)
	v_lshlrev_b32_e32 v122, 16, v114
	v_mul_f32_e32 v118, v118, v122
	v_max_f32_e32 v122, 0, v125
	v_and_b32_e32 v114, 0xffff0000, v114
	v_sqrt_f32_e32 v122, v122
	v_mul_f32_e32 v114, v119, v114
	v_mul_f32_e32 v112, 0x42000000, v118
	v_mul_f32_e32 v113, 0x42000000, v114
	v_med3_f32 v112, v112, s29, v231
	v_med3_f32 v113, v113, s29, v231
	v_mov_b32_e32 v114, 0
	v_lshlrev_b32_e32 v123, 16, v115
	v_and_b32_e32 v115, 0xffff0000, v115
	v_mul_f32_e32 v119, v120, v124
	v_mul_f32_e32 v120, v121, v122
	v_cvt_pk_fp8_f32 v114, v112, v113
	v_mul_f32_e32 v119, v119, v123
	v_mul_f32_e32 v115, v120, v115
	v_mul_f32_e32 v118, 0x42000000, v119
	v_mul_f32_e32 v112, 0x42000000, v115
	v_med3_f32 v113, v118, s29, v231
	v_med3_f32 v112, v112, s29, v231
	v_mul_f32_e32 v102, v102, v130
	v_cvt_pk_fp8_f32 v114, v113, v112 op_sel:[0,0,1]
	v_lshlrev_b32_e32 v112, 16, v116
	v_and_b32_e32 v113, 0xffff0000, v116
	v_add_f32_e32 v116, v102, v102
	v_add_f32_e32 v103, v103, v31
	v_add_f32_e32 v98, v98, v26
	v_mul_f32_e32 v116, 0x3fb8aa3b, v116
	v_mul_f32_e32 v103, 0xbfb8aa3b, v103
	v_mul_f32_e32 v98, 0xbfb8aa3b, v98
	v_exp_f32_e32 v116, v116
	v_exp_f32_e32 v103, v103
	v_exp_f32_e32 v98, v98
	v_add_f32_e32 v104, v104, v32
	v_sub_f32_e32 v116, 1.0, v116
	v_add_f32_e32 v103, 1.0, v103
	v_add_f32_e32 v98, 1.0, v98
	v_max_f32_e32 v116, 0, v116
	v_rcp_f32_e32 v103, v103
	v_rcp_f32_e32 v98, v98
	v_sqrt_f32_e32 v116, v116
	v_add_f32_e32 v105, v105, v33
	v_mul_f32_e32 v103, v103, v131
	v_add_f32_e32 v99, v99, v27
	v_mul_f32_e32 v98, v98, v116
	v_add_f32_e32 v116, v103, v103
	v_mul_f32_e32 v116, 0x3fb8aa3b, v116
	v_mul_f32_e32 v104, 0xbfb8aa3b, v104
	v_mul_f32_e32 v105, 0xbfb8aa3b, v105
	v_mul_f32_e32 v99, 0xbfb8aa3b, v99
	v_exp_f32_e32 v116, v116
	v_exp_f32_e32 v104, v104
	v_exp_f32_e32 v105, v105
	v_exp_f32_e32 v99, v99
	v_sub_f32_e32 v116, 1.0, v116
	v_add_f32_e32 v104, 1.0, v104
	v_add_f32_e32 v105, 1.0, v105
	v_add_f32_e32 v99, 1.0, v99
	v_max_f32_e32 v116, 0, v116
	v_rcp_f32_e32 v104, v104
	v_rcp_f32_e32 v105, v105
	v_rcp_f32_e32 v99, v99
	v_sqrt_f32_e32 v116, v116
	v_mul_f32_e32 v104, v104, v132
	v_mul_f32_e32 v105, v105, v133
	v_mul_f32_e32 v98, v98, v112
	v_mul_f32_e32 v99, v99, v116
	v_add_f32_e32 v112, v104, v104
	v_add_f32_e32 v116, v105, v105
	v_add_f32_e32 v100, v100, v28
	v_mul_f32_e32 v112, 0x3fb8aa3b, v112
	v_add_f32_e32 v101, v101, v29
	v_mul_f32_e32 v116, 0x3fb8aa3b, v116
	v_mul_f32_e32 v100, 0xbfb8aa3b, v100
	v_exp_f32_e32 v112, v112
	v_mul_f32_e32 v101, 0xbfb8aa3b, v101
	v_exp_f32_e32 v116, v116
	v_add_f32_e32 v94, v94, v46
	v_exp_f32_e32 v100, v100
	v_exp_f32_e32 v101, v101
	v_mul_f32_e32 v94, 0xbfb8aa3b, v94
	v_exp_f32_e32 v94, v94
	v_sub_f32_e32 v112, 1.0, v112
	v_sub_f32_e32 v116, 1.0, v116
	v_add_f32_e32 v100, 1.0, v100
	v_max_f32_e32 v112, 0, v112
	v_add_f32_e32 v101, 1.0, v101
	v_max_f32_e32 v116, 0, v116
	v_rcp_f32_e32 v100, v100
	v_sqrt_f32_e32 v112, v112
	v_rcp_f32_e32 v101, v101
	v_sqrt_f32_e32 v116, v116
	v_add_f32_e32 v94, 1.0, v94
	v_rcp_f32_e32 v94, v94
	v_mul_f32_e32 v99, v99, v113
	v_lshlrev_b32_e32 v115, 16, v117
	v_and_b32_e32 v117, 0xffff0000, v117
	v_mul_f32_e32 v100, v100, v112
	v_mul_f32_e32 v101, v101, v116
	v_mul_f32_e32 v98, 0x42000000, v98
	v_mul_f32_e32 v99, 0x42000000, v99
	v_mul_f32_e32 v100, v100, v115
	v_mul_f32_e32 v101, v101, v117
	v_med3_f32 v98, v98, s29, v231
	v_med3_f32 v99, v99, s29, v231
	v_mov_b32_e32 v115, 0
	v_mul_f32_e32 v94, v94, v144
	v_cvt_pk_fp8_f32 v115, v98, v99
	v_mul_f32_e32 v98, 0x42000000, v101
	v_add_f32_e32 v101, v94, v94
	v_add_f32_e32 v95, v95, v47
	v_add_f32_e32 v90, v90, v42
	v_mul_f32_e32 v101, 0x3fb8aa3b, v101
	v_mul_f32_e32 v95, 0xbfb8aa3b, v95
	v_mul_f32_e32 v90, 0xbfb8aa3b, v90
	v_exp_f32_e32 v101, v101
	v_exp_f32_e32 v95, v95
	v_exp_f32_e32 v90, v90
	v_add_f32_e32 v91, v91, v43
	v_sub_f32_e32 v101, 1.0, v101
	v_add_f32_e32 v95, 1.0, v95
	v_add_f32_e32 v90, 1.0, v90
	v_max_f32_e32 v101, 0, v101
	v_rcp_f32_e32 v95, v95
	v_rcp_f32_e32 v90, v90
	v_sqrt_f32_e32 v101, v101
	v_add_f32_e32 v96, v96, v48
	v_mul_f32_e32 v95, v95, v145
	v_mul_f32_e32 v91, 0xbfb8aa3b, v91
	v_mul_f32_e32 v90, v90, v101
	v_add_f32_e32 v101, v95, v95
	v_mul_f32_e32 v101, 0x3fb8aa3b, v101
	v_exp_f32_e32 v101, v101
	v_mul_f32_e32 v96, 0xbfb8aa3b, v96
	v_add_f32_e32 v97, v97, v49
	v_exp_f32_e32 v91, v91
	v_exp_f32_e32 v96, v96
	v_mul_f32_e32 v97, 0xbfb8aa3b, v97
	v_exp_f32_e32 v97, v97
	v_mul_f32_e32 v100, 0x42000000, v100
	v_med3_f32 v99, v100, s29, v231
	v_med3_f32 v98, v98, s29, v231
	v_sub_f32_e32 v101, 1.0, v101
	v_add_f32_e32 v92, v92, v44
	v_cvt_pk_fp8_f32 v115, v99, v98 op_sel:[0,0,1]
	v_add_co_u32_e32 v98, vcc, s92, v172
	v_add_f32_e32 v91, 1.0, v91
	v_max_f32_e32 v101, 0, v101
	v_add_f32_e32 v96, 1.0, v96
	v_mul_f32_e32 v92, 0xbfb8aa3b, v92
	v_cvt_pk_bf16_f32 v112, v102, v103
	v_cvt_pk_bf16_f32 v113, v104, v105
	v_addc_co_u32_e32 v99, vcc, 0, v173, vcc
	v_rcp_f32_e32 v91, v91
	v_sqrt_f32_e32 v101, v101
	v_exp_f32_e32 v92, v92
	v_rcp_f32_e32 v96, v96
	v_add_f32_e32 v97, 1.0, v97
	global_store_dwordx4 v[98:99], v[110:113], off
	v_add_co_u32_e32 v98, vcc, s84, v170
	v_rcp_f32_e32 v97, v97
	s_nop 0
	v_addc_co_u32_e32 v99, vcc, 0, v171, vcc
	global_store_dwordx2 v[98:99], v[114:115], off
	v_lshlrev_b32_e32 v98, 16, v106
	v_mul_f32_e32 v98, v90, v98
	v_mul_f32_e32 v90, v91, v101
	v_add_f32_e32 v91, 1.0, v92
	v_mul_f32_e32 v92, v96, v142
	v_add_f32_e32 v96, v92, v92
	v_mul_f32_e32 v97, v97, v143
	v_mul_f32_e32 v96, 0x3fb8aa3b, v96
	v_add_f32_e32 v101, v97, v97
	v_exp_f32_e32 v96, v96
	v_add_f32_e32 v93, v93, v45
	v_mul_f32_e32 v101, 0x3fb8aa3b, v101
	v_mul_f32_e32 v93, 0xbfb8aa3b, v93
	v_exp_f32_e32 v101, v101
	v_exp_f32_e32 v93, v93
	v_add_f32_e32 v86, v86, v30
	v_mul_f32_e32 v86, 0xbfb8aa3b, v86
	v_sub_f32_e32 v96, 1.0, v96
	v_exp_f32_e32 v86, v86
	v_max_f32_e32 v96, 0, v96
	v_sub_f32_e32 v101, 1.0, v101
	v_rcp_f32_e32 v91, v91
	v_sqrt_f32_e32 v96, v96
	v_add_f32_e32 v93, 1.0, v93
	v_max_f32_e32 v101, 0, v101
	v_rcp_f32_e32 v93, v93
	v_sqrt_f32_e32 v101, v101
	v_add_f32_e32 v86, 1.0, v86
	v_and_b32_e32 v99, 0xffff0000, v106
	v_rcp_f32_e32 v86, v86
	v_lshlrev_b32_e32 v100, 16, v107
	v_mul_f32_e32 v99, v90, v99
	v_mul_f32_e32 v90, v91, v96
	v_and_b32_e32 v102, 0xffff0000, v107
	v_mul_f32_e32 v96, v90, v100
	v_mul_f32_e32 v90, v93, v101
	v_mul_f32_e32 v93, v90, v102
	v_cvt_pk_bf16_f32 v90, v94, v95
	v_cvt_pk_bf16_f32 v91, v92, v97
	v_mul_f32_e32 v92, 0x42000000, v98
	v_mul_f32_e32 v94, 0x42000000, v99
	v_mul_f32_e32 v95, 0x42000000, v96
	v_med3_f32 v92, v92, s29, v231
	v_med3_f32 v96, v94, s29, v231
	v_mov_b32_e32 v94, 0
	v_mul_f32_e32 v86, v86, v130
	v_cvt_pk_fp8_f32 v94, v92, v96
	v_add_f32_e32 v96, v86, v86
	v_add_f32_e32 v87, v87, v31
	v_add_f32_e32 v82, v82, v26
	v_mul_f32_e32 v96, 0x3fb8aa3b, v96
	v_mul_f32_e32 v87, 0xbfb8aa3b, v87
	v_mul_f32_e32 v82, 0xbfb8aa3b, v82
	v_exp_f32_e32 v96, v96
	v_exp_f32_e32 v87, v87
	v_exp_f32_e32 v82, v82
	v_add_f32_e32 v88, v88, v32
	v_sub_f32_e32 v96, 1.0, v96
	v_add_f32_e32 v87, 1.0, v87
	v_add_f32_e32 v82, 1.0, v82
	v_max_f32_e32 v96, 0, v96
	v_rcp_f32_e32 v87, v87
	v_rcp_f32_e32 v82, v82
	v_sqrt_f32_e32 v96, v96
	v_mul_f32_e32 v88, 0xbfb8aa3b, v88
	v_mul_f32_e32 v87, v87, v131
	v_exp_f32_e32 v88, v88
	v_mul_f32_e32 v82, v82, v96
	v_add_f32_e32 v96, v87, v87
	v_add_f32_e32 v89, v89, v33
	v_add_f32_e32 v83, v83, v27
	v_mul_f32_e32 v96, 0x3fb8aa3b, v96
	v_mul_f32_e32 v89, 0xbfb8aa3b, v89
	v_mul_f32_e32 v83, 0xbfb8aa3b, v83
	v_exp_f32_e32 v96, v96
	v_exp_f32_e32 v89, v89
	v_exp_f32_e32 v83, v83
	v_add_f32_e32 v88, 1.0, v88
	v_rcp_f32_e32 v88, v88
	v_sub_f32_e32 v96, 1.0, v96
	v_add_f32_e32 v89, 1.0, v89
	v_mul_f32_e32 v92, 0x42000000, v93
	v_add_f32_e32 v83, 1.0, v83
	v_max_f32_e32 v96, 0, v96
	v_rcp_f32_e32 v89, v89
	v_med3_f32 v93, v95, s29, v231
	v_med3_f32 v92, v92, s29, v231
	v_rcp_f32_e32 v83, v83
	v_sqrt_f32_e32 v96, v96
	v_cvt_pk_fp8_f32 v94, v93, v92 op_sel:[0,0,1]
	v_lshlrev_b32_e32 v92, 16, v108
	v_mul_f32_e32 v88, v88, v132
	v_mul_f32_e32 v82, v82, v92
	v_add_f32_e32 v92, v88, v88
	v_add_f32_e32 v84, v84, v28
	v_mul_f32_e32 v92, 0x3fb8aa3b, v92
	v_mul_f32_e32 v89, v89, v133
	v_mul_f32_e32 v84, 0xbfb8aa3b, v84
	v_mul_f32_e32 v83, v83, v96
	v_exp_f32_e32 v92, v92
	v_add_f32_e32 v96, v89, v89
	v_exp_f32_e32 v84, v84
	v_add_f32_e32 v85, v85, v29
	v_mul_f32_e32 v96, 0x3fb8aa3b, v96
	v_mul_f32_e32 v85, 0xbfb8aa3b, v85
	v_exp_f32_e32 v96, v96
	v_exp_f32_e32 v85, v85
	v_sub_f32_e32 v92, 1.0, v92
	v_add_f32_e32 v84, 1.0, v84
	v_max_f32_e32 v92, 0, v92
	v_rcp_f32_e32 v84, v84
	v_sqrt_f32_e32 v92, v92
	v_sub_f32_e32 v96, 1.0, v96
	v_add_f32_e32 v85, 1.0, v85
	v_max_f32_e32 v96, 0, v96
	v_and_b32_e32 v93, 0xffff0000, v108
	v_rcp_f32_e32 v85, v85
	v_sqrt_f32_e32 v96, v96
	v_mul_f32_e32 v83, v83, v93
	v_lshlrev_b32_e32 v95, 16, v109
	v_mul_f32_e32 v84, v84, v92
	v_mul_f32_e32 v82, 0x42000000, v82
	v_mul_f32_e32 v83, 0x42000000, v83
	v_mul_f32_e32 v84, v84, v95
	v_med3_f32 v82, v82, s29, v231
	v_med3_f32 v83, v83, s29, v231
	v_mov_b32_e32 v95, 0
	v_and_b32_e32 v97, 0xffff0000, v109
	v_mul_f32_e32 v85, v85, v96
	v_cvt_pk_fp8_f32 v95, v82, v83
	v_mul_f32_e32 v85, v85, v97
	v_mul_f32_e32 v84, 0x42000000, v84
	v_mul_f32_e32 v82, 0x42000000, v85
	v_med3_f32 v83, v84, s29, v231
	v_med3_f32 v82, v82, s29, v231
	v_cvt_pk_fp8_f32 v95, v83, v82 op_sel:[0,0,1]
	v_add_co_u32_e32 v82, vcc, s89, v172
	v_cvt_pk_bf16_f32 v92, v86, v87
	v_cvt_pk_bf16_f32 v93, v88, v89
	v_addc_co_u32_e32 v83, vcc, 0, v173, vcc
	s_mov_b32 s0, 0xc000
	global_store_dwordx4 v[82:83], v[90:93], off
	v_add_co_u32_e32 v82, vcc, s0, v170
	s_nop 1
	v_addc_co_u32_e32 v83, vcc, 0, v171, vcc
	global_store_dwordx2 v[82:83], v[94:95], off
	v_add_u32_e32 v82, 0x80, v234
	v_add_f32_e32 v78, v78, v46
	v_ashrrev_i32_e32 v83, 31, v82
	v_lshlrev_b64 v[82:83], 10, v[82:83]
	v_lshl_add_u64 v[88:89], v[82:83], 0, v[166:167]
	v_lshlrev_b64 v[90:91], 1, v[88:89]
	v_lshl_add_u64 v[82:83], s[24:25], 0, v[90:91]
	global_load_dwordx4 v[84:87], v[82:83], off
	v_mul_f32_e32 v78, 0xbfb8aa3b, v78
	v_exp_f32_e32 v92, v78
	v_add_f32_e32 v79, v79, v47
	v_add_f32_e32 v80, v80, v48
	v_mul_f32_e32 v79, 0xbfb8aa3b, v79
	v_add_f32_e32 v74, v74, v42
	v_add_f32_e32 v81, v81, v49
	v_mul_f32_e32 v80, 0xbfb8aa3b, v80
	v_exp_f32_e32 v93, v79
	v_add_f32_e32 v75, v75, v43
	v_add_f32_e32 v76, v76, v44
	v_add_f32_e32 v77, v77, v45
	v_mul_f32_e32 v74, 0xbfb8aa3b, v74
	v_mul_f32_e32 v81, 0xbfb8aa3b, v81
	v_exp_f32_e32 v94, v80
	v_lshl_add_u64 v[78:79], s[50:51], 0, v[88:89]
	v_add_f32_e32 v88, 1.0, v92
	v_mul_f32_e32 v75, 0xbfb8aa3b, v75
	v_mul_f32_e32 v76, 0xbfb8aa3b, v76
	v_mul_f32_e32 v77, 0xbfb8aa3b, v77
	v_exp_f32_e32 v74, v74
	v_exp_f32_e32 v95, v81
	v_rcp_f32_e32 v88, v88
	v_exp_f32_e32 v75, v75
	v_exp_f32_e32 v76, v76
	v_exp_f32_e32 v77, v77
	v_lshl_add_u64 v[80:81], s[48:49], 0, v[90:91]
	v_add_f32_e32 v90, 1.0, v93
	v_add_f32_e32 v92, 1.0, v94
	v_rcp_f32_e32 v90, v90
	v_add_f32_e32 v89, 1.0, v74
	v_add_f32_e32 v93, 1.0, v95
	v_add_co_u32_e32 v74, vcc, s84, v82
	v_rcp_f32_e32 v92, v92
	v_mul_f32_e32 v88, v88, v144
	v_add_f32_e32 v91, 1.0, v75
	v_add_f32_e32 v76, 1.0, v76
	v_add_f32_e32 v77, 1.0, v77
	v_addc_co_u32_e32 v75, vcc, 0, v83, vcc
	v_rcp_f32_e32 v93, v93
	v_add_f32_e32 v96, v88, v88
	v_rcp_f32_e32 v94, v76
	v_rcp_f32_e32 v95, v77
	global_load_dwordx4 v[74:77], v[74:75], off
	v_mul_f32_e32 v96, 0x3fb8aa3b, v96
	v_mul_f32_e32 v90, v90, v145
	v_exp_f32_e32 v96, v96
	v_mul_f32_e32 v92, v92, v142
	v_add_f32_e32 v97, v90, v90
	v_mul_f32_e32 v93, v93, v143
	v_add_f32_e32 v98, v92, v92
	v_mul_f32_e32 v97, 0x3fb8aa3b, v97
	v_add_f32_e32 v99, v93, v93
	v_mul_f32_e32 v98, 0x3fb8aa3b, v98
	v_exp_f32_e32 v97, v97
	v_mul_f32_e32 v99, 0x3fb8aa3b, v99
	v_exp_f32_e32 v98, v98
	v_sub_f32_e32 v96, 1.0, v96
	v_exp_f32_e32 v99, v99
	v_max_f32_e32 v96, 0, v96
	v_rcp_f32_e32 v89, v89
	v_sqrt_f32_e32 v96, v96
	v_add_f32_e32 v70, v70, v30
	v_sub_f32_e32 v97, 1.0, v97
	v_mul_f32_e32 v70, 0xbfb8aa3b, v70
	v_sub_f32_e32 v98, 1.0, v98
	v_max_f32_e32 v97, 0, v97
	v_exp_f32_e32 v70, v70
	v_rcp_f32_e32 v91, v91
	v_sub_f32_e32 v99, 1.0, v99
	v_max_f32_e32 v98, 0, v98
	v_sqrt_f32_e32 v97, v97
	v_max_f32_e32 v99, 0, v99
	v_sqrt_f32_e32 v98, v98
	v_mul_f32_e32 v89, v89, v96
	v_add_f32_e32 v70, 1.0, v70
	v_mul_f32_e32 v91, v91, v97
	s_waitcnt vmcnt(0) lgkmcnt(0)
	v_lshlrev_b32_e32 v96, 16, v84
	v_mul_f32_e32 v89, v89, v96
	v_sqrt_f32_e32 v96, v99
	v_and_b32_e32 v84, 0xffff0000, v84
	v_rcp_f32_e32 v70, v70
	v_lshlrev_b32_e32 v97, 16, v85
	v_mul_f32_e32 v91, v91, v84
	v_mul_f32_e32 v84, v94, v98
	v_and_b32_e32 v85, 0xffff0000, v85
	v_mul_f32_e32 v94, v84, v97
	v_mul_f32_e32 v84, v95, v96
	v_mul_f32_e32 v95, v84, v85
	v_cvt_pk_bf16_f32 v84, v88, v90
	v_mul_f32_e32 v88, 0x42000000, v89
	v_mul_f32_e32 v89, 0x42000000, v91
	v_med3_f32 v91, v88, s29, v231
	v_med3_f32 v89, v89, s29, v231
	v_mov_b32_e32 v88, 0
	v_mul_f32_e32 v70, v70, v130
	v_cvt_pk_fp8_f32 v88, v91, v89
	v_add_f32_e32 v91, v70, v70
	v_add_f32_e32 v71, v71, v31
	v_add_f32_e32 v66, v66, v26
	v_mul_f32_e32 v91, 0x3fb8aa3b, v91
	v_mul_f32_e32 v71, 0xbfb8aa3b, v71
	v_mul_f32_e32 v66, 0xbfb8aa3b, v66
	v_exp_f32_e32 v91, v91
	v_exp_f32_e32 v71, v71
	v_exp_f32_e32 v66, v66
	v_add_f32_e32 v73, v73, v33
	v_sub_f32_e32 v91, 1.0, v91
	v_add_f32_e32 v71, 1.0, v71
	v_add_f32_e32 v66, 1.0, v66
	v_max_f32_e32 v91, 0, v91
	v_rcp_f32_e32 v71, v71
	v_rcp_f32_e32 v66, v66
	v_sqrt_f32_e32 v91, v91
	v_add_f32_e32 v67, v67, v27
	v_mul_f32_e32 v71, v71, v131
	v_add_f32_e32 v72, v72, v32
	v_mul_f32_e32 v66, v66, v91
	v_add_f32_e32 v91, v71, v71
	v_mul_f32_e32 v91, 0x3fb8aa3b, v91
	v_mul_f32_e32 v73, 0xbfb8aa3b, v73
	v_mul_f32_e32 v67, 0xbfb8aa3b, v67
	v_exp_f32_e32 v91, v91
	v_mul_f32_e32 v72, 0xbfb8aa3b, v72
	v_exp_f32_e32 v73, v73
	v_exp_f32_e32 v67, v67
	v_exp_f32_e32 v72, v72
	v_sub_f32_e32 v91, 1.0, v91
	v_add_f32_e32 v73, 1.0, v73
	v_add_f32_e32 v67, 1.0, v67
	v_max_f32_e32 v91, 0, v91
	v_add_f32_e32 v72, 1.0, v72
	v_rcp_f32_e32 v73, v73
	v_rcp_f32_e32 v67, v67
	v_sqrt_f32_e32 v91, v91
	v_rcp_f32_e32 v72, v72
	v_mul_f32_e32 v90, 0x42000000, v94
	v_mul_f32_e32 v89, 0x42000000, v95
	v_med3_f32 v90, v90, s29, v231
	v_med3_f32 v89, v89, s29, v231
	v_mul_f32_e32 v73, v73, v133
	v_cvt_pk_fp8_f32 v88, v90, v89 op_sel:[0,0,1]
	v_lshlrev_b32_e32 v89, 16, v86
	v_mul_f32_e32 v67, v67, v91
	v_mul_f32_e32 v72, v72, v132
	v_add_f32_e32 v91, v73, v73
	v_mul_f32_e32 v66, v66, v89
	v_add_f32_e32 v89, v72, v72
	v_add_f32_e32 v69, v69, v29
	v_mul_f32_e32 v91, 0x3fb8aa3b, v91
	v_add_f32_e32 v68, v68, v28
	v_mul_f32_e32 v89, 0x3fb8aa3b, v89
	v_mul_f32_e32 v69, 0xbfb8aa3b, v69
	v_exp_f32_e32 v91, v91
	v_add_f32_e32 v62, v62, v46
	v_mul_f32_e32 v68, 0xbfb8aa3b, v68
	v_exp_f32_e32 v89, v89
	v_exp_f32_e32 v69, v69
	v_mul_f32_e32 v62, 0xbfb8aa3b, v62
	v_exp_f32_e32 v68, v68
	v_exp_f32_e32 v62, v62
	v_sub_f32_e32 v91, 1.0, v91
	v_sub_f32_e32 v89, 1.0, v89
	v_add_f32_e32 v69, 1.0, v69
	v_max_f32_e32 v91, 0, v91
	v_add_f32_e32 v68, 1.0, v68
	v_max_f32_e32 v89, 0, v89
	v_rcp_f32_e32 v69, v69
	v_sqrt_f32_e32 v91, v91
	v_add_f32_e32 v62, 1.0, v62
	v_rcp_f32_e32 v68, v68
	v_sqrt_f32_e32 v89, v89
	v_rcp_f32_e32 v62, v62
	v_and_b32_e32 v86, 0xffff0000, v86
	v_mul_f32_e32 v67, v67, v86
	v_lshlrev_b32_e32 v90, 16, v87
	v_and_b32_e32 v87, 0xffff0000, v87
	v_mul_f32_e32 v69, v69, v91
	v_mul_f32_e32 v66, 0x42000000, v66
	v_mul_f32_e32 v67, 0x42000000, v67
	v_mul_f32_e32 v68, v68, v89
	v_mul_f32_e32 v69, v69, v87
	v_med3_f32 v66, v66, s29, v231
	v_med3_f32 v67, v67, s29, v231
	v_mov_b32_e32 v89, 0
	v_mul_f32_e32 v62, v62, v144
	v_cvt_pk_fp8_f32 v89, v66, v67
	v_mul_f32_e32 v66, 0x42000000, v69
	v_add_f32_e32 v69, v62, v62
	v_add_f32_e32 v63, v63, v47
	v_add_f32_e32 v58, v58, v42
	v_mul_f32_e32 v69, 0x3fb8aa3b, v69
	v_mul_f32_e32 v63, 0xbfb8aa3b, v63
	v_mul_f32_e32 v58, 0xbfb8aa3b, v58
	v_exp_f32_e32 v69, v69
	v_exp_f32_e32 v63, v63
	v_exp_f32_e32 v58, v58
	v_add_f32_e32 v59, v59, v43
	v_sub_f32_e32 v69, 1.0, v69
	v_add_f32_e32 v63, 1.0, v63
	v_add_f32_e32 v58, 1.0, v58
	v_max_f32_e32 v69, 0, v69
	v_rcp_f32_e32 v63, v63
	v_rcp_f32_e32 v58, v58
	v_sqrt_f32_e32 v69, v69
	v_add_f32_e32 v64, v64, v48
	v_mul_f32_e32 v63, v63, v145
	v_mul_f32_e32 v59, 0xbfb8aa3b, v59
	v_mul_f32_e32 v58, v58, v69
	v_add_f32_e32 v69, v63, v63
	v_mul_f32_e32 v69, 0x3fb8aa3b, v69
	v_exp_f32_e32 v69, v69
	v_mul_f32_e32 v64, 0xbfb8aa3b, v64
	v_add_f32_e32 v65, v65, v49
	v_exp_f32_e32 v59, v59
	v_exp_f32_e32 v64, v64
	v_mul_f32_e32 v65, 0xbfb8aa3b, v65
	v_exp_f32_e32 v65, v65
	v_sub_f32_e32 v69, 1.0, v69
	v_add_f32_e32 v60, v60, v44
	v_add_f32_e32 v59, 1.0, v59
	v_max_f32_e32 v69, 0, v69
	v_add_f32_e32 v64, 1.0, v64
	v_mul_f32_e32 v60, 0xbfb8aa3b, v60
	v_mul_f32_e32 v68, v68, v90
	v_rcp_f32_e32 v59, v59
	v_sqrt_f32_e32 v69, v69
	v_exp_f32_e32 v60, v60
	v_rcp_f32_e32 v64, v64
	v_add_f32_e32 v65, 1.0, v65
	v_mul_f32_e32 v68, 0x42000000, v68
	v_rcp_f32_e32 v65, v65
	v_med3_f32 v67, v68, s29, v231
	v_med3_f32 v66, v66, s29, v231
	v_cvt_pk_fp8_f32 v89, v67, v66 op_sel:[0,0,1]
	v_lshlrev_b32_e32 v66, 16, v74
	v_mul_f32_e32 v66, v58, v66
	v_mul_f32_e32 v58, v59, v69
	v_add_f32_e32 v59, 1.0, v60
	v_mul_f32_e32 v60, v64, v142
	v_add_f32_e32 v64, v60, v60
	v_mul_f32_e32 v65, v65, v143
	v_mul_f32_e32 v64, 0x3fb8aa3b, v64
	v_add_f32_e32 v69, v65, v65
	v_exp_f32_e32 v64, v64
	v_add_f32_e32 v61, v61, v45
	v_mul_f32_e32 v69, 0x3fb8aa3b, v69
	v_mul_f32_e32 v61, 0xbfb8aa3b, v61
	v_exp_f32_e32 v69, v69
	v_exp_f32_e32 v61, v61
	v_add_f32_e32 v54, v54, v30
	v_mul_f32_e32 v54, 0xbfb8aa3b, v54
	v_sub_f32_e32 v64, 1.0, v64
	v_exp_f32_e32 v54, v54
	v_max_f32_e32 v64, 0, v64
	v_sub_f32_e32 v69, 1.0, v69
	v_rcp_f32_e32 v59, v59
	v_sqrt_f32_e32 v64, v64
	v_add_f32_e32 v61, 1.0, v61
	v_max_f32_e32 v69, 0, v69
	v_rcp_f32_e32 v61, v61
	v_sqrt_f32_e32 v69, v69
	v_add_f32_e32 v54, 1.0, v54
	v_and_b32_e32 v67, 0xffff0000, v74
	v_rcp_f32_e32 v54, v54
	v_lshlrev_b32_e32 v68, 16, v75
	v_mul_f32_e32 v67, v58, v67
	v_mul_f32_e32 v58, v59, v64
	v_cvt_pk_bf16_f32 v86, v70, v71
	v_and_b32_e32 v70, 0xffff0000, v75
	v_mul_f32_e32 v64, v58, v68
	v_mul_f32_e32 v58, v61, v69
	v_mul_f32_e32 v61, v58, v70
	v_cvt_pk_bf16_f32 v58, v62, v63
	v_cvt_pk_bf16_f32 v59, v60, v65
	v_mul_f32_e32 v60, 0x42000000, v66
	v_mul_f32_e32 v62, 0x42000000, v67
	v_mul_f32_e32 v63, 0x42000000, v64
	v_med3_f32 v60, v60, s29, v231
	v_med3_f32 v64, v62, s29, v231
	v_mov_b32_e32 v62, 0
	v_mul_f32_e32 v54, v54, v130
	v_cvt_pk_fp8_f32 v62, v60, v64
	v_add_f32_e32 v64, v54, v54
	v_add_f32_e32 v55, v55, v31
	v_add_f32_e32 v50, v50, v26
	v_mul_f32_e32 v64, 0x3fb8aa3b, v64
	v_mul_f32_e32 v55, 0xbfb8aa3b, v55
	v_mul_f32_e32 v50, 0xbfb8aa3b, v50
	v_exp_f32_e32 v64, v64
	v_exp_f32_e32 v55, v55
	v_exp_f32_e32 v50, v50
	v_add_f32_e32 v56, v56, v32
	v_sub_f32_e32 v64, 1.0, v64
	v_add_f32_e32 v55, 1.0, v55
	v_add_f32_e32 v50, 1.0, v50
	v_max_f32_e32 v64, 0, v64
	v_rcp_f32_e32 v55, v55
	v_rcp_f32_e32 v50, v50
	v_sqrt_f32_e32 v64, v64
	v_mul_f32_e32 v56, 0xbfb8aa3b, v56
	v_mul_f32_e32 v55, v55, v131
	v_exp_f32_e32 v56, v56
	v_mul_f32_e32 v50, v50, v64
	v_add_f32_e32 v64, v55, v55
	v_add_f32_e32 v57, v57, v33
	v_add_f32_e32 v51, v51, v27
	v_mul_f32_e32 v64, 0x3fb8aa3b, v64
	v_mul_f32_e32 v57, 0xbfb8aa3b, v57
	v_mul_f32_e32 v51, 0xbfb8aa3b, v51
	v_exp_f32_e32 v64, v64
	v_exp_f32_e32 v57, v57
	v_exp_f32_e32 v51, v51
	v_add_f32_e32 v56, 1.0, v56
	v_rcp_f32_e32 v56, v56
	v_sub_f32_e32 v64, 1.0, v64
	v_add_f32_e32 v57, 1.0, v57
	v_mul_f32_e32 v60, 0x42000000, v61
	v_add_f32_e32 v51, 1.0, v51
	v_max_f32_e32 v64, 0, v64
	v_rcp_f32_e32 v57, v57
	v_med3_f32 v61, v63, s29, v231
	v_med3_f32 v60, v60, s29, v231
	v_rcp_f32_e32 v51, v51
	v_sqrt_f32_e32 v64, v64
	v_cvt_pk_fp8_f32 v62, v61, v60 op_sel:[0,0,1]
	v_lshlrev_b32_e32 v60, 16, v76
	v_mul_f32_e32 v56, v56, v132
	v_mul_f32_e32 v50, v50, v60
	v_add_f32_e32 v60, v56, v56
	v_add_f32_e32 v52, v52, v28
	v_mul_f32_e32 v60, 0x3fb8aa3b, v60
	v_mul_f32_e32 v57, v57, v133
	v_mul_f32_e32 v52, 0xbfb8aa3b, v52
	v_mul_f32_e32 v51, v51, v64
	v_exp_f32_e32 v60, v60
	v_add_f32_e32 v64, v57, v57
	v_exp_f32_e32 v52, v52
	v_add_f32_e32 v53, v53, v29
	v_mul_f32_e32 v64, 0x3fb8aa3b, v64
	v_mul_f32_e32 v53, 0xbfb8aa3b, v53
	v_exp_f32_e32 v64, v64
	v_exp_f32_e32 v53, v53
	v_sub_f32_e32 v60, 1.0, v60
	v_add_f32_e32 v52, 1.0, v52
	v_max_f32_e32 v60, 0, v60
	v_rcp_f32_e32 v52, v52
	v_sqrt_f32_e32 v60, v60
	v_sub_f32_e32 v64, 1.0, v64
	v_add_f32_e32 v53, 1.0, v53
	v_max_f32_e32 v64, 0, v64
	v_and_b32_e32 v61, 0xffff0000, v76
	v_rcp_f32_e32 v53, v53
	v_sqrt_f32_e32 v64, v64
	v_mul_f32_e32 v51, v51, v61
	v_lshlrev_b32_e32 v63, 16, v77
	v_mul_f32_e32 v52, v52, v60
	v_mul_f32_e32 v50, 0x42000000, v50
	v_mul_f32_e32 v51, 0x42000000, v51
	v_mul_f32_e32 v52, v52, v63
	v_med3_f32 v50, v50, s29, v231
	v_med3_f32 v51, v51, s29, v231
	v_mov_b32_e32 v63, 0
	v_and_b32_e32 v65, 0xffff0000, v77
	v_mul_f32_e32 v53, v53, v64
	v_cvt_pk_fp8_f32 v63, v50, v51
	v_mul_f32_e32 v53, v53, v65
	v_mul_f32_e32 v52, 0x42000000, v52
	v_mul_f32_e32 v50, 0x42000000, v53
	v_med3_f32 v51, v52, s29, v231
	v_med3_f32 v50, v50, s29, v231
	v_cvt_pk_fp8_f32 v63, v51, v50 op_sel:[0,0,1]
	v_add_co_u32_e32 v50, vcc, s84, v80
	v_cvt_pk_bf16_f32 v85, v92, v93
	v_cvt_pk_bf16_f32 v87, v72, v73
	v_cvt_pk_bf16_f32 v60, v54, v55
	v_cvt_pk_bf16_f32 v61, v56, v57
	v_addc_co_u32_e32 v51, vcc, 0, v81, vcc
	global_store_dwordx4 v[80:81], v[84:87], off
	global_store_dwordx2 v[78:79], v[88:89], off
	global_store_dwordx4 v[50:51], v[58:61], off
	v_add_co_u32_e32 v50, vcc, s93, v78
	s_nop 1
	v_addc_co_u32_e32 v51, vcc, 0, v79, vcc
	global_store_dwordx2 v[50:51], v[62:63], off
	v_add_co_u32_e32 v50, vcc, s92, v82
	v_add_f32_e32 v38, v38, v46
	s_nop 0
	v_addc_co_u32_e32 v51, vcc, 0, v83, vcc
	global_load_dwordx4 v[54:57], v[50:51], off
	v_mul_f32_e32 v38, 0xbfb8aa3b, v38
	v_exp_f32_e32 v38, v38
	v_add_f32_e32 v34, v34, v42
	v_mul_f32_e32 v34, 0xbfb8aa3b, v34
	v_exp_f32_e32 v34, v34
	v_add_f32_e32 v38, 1.0, v38
	v_rcp_f32_e32 v38, v38
	v_add_f32_e32 v39, v39, v47
	v_add_f32_e32 v34, 1.0, v34
	v_mul_f32_e32 v39, 0xbfb8aa3b, v39
	v_exp_f32_e32 v39, v39
	v_add_f32_e32 v35, v35, v43
	v_mul_f32_e32 v35, 0xbfb8aa3b, v35
	v_exp_f32_e32 v35, v35
	v_add_f32_e32 v39, 1.0, v39
	v_rcp_f32_e32 v39, v39
	v_add_f32_e32 v36, v36, v44
	v_add_f32_e32 v35, 1.0, v35
	v_rcp_f32_e32 v35, v35
	v_mul_f32_e32 v39, v39, v145
	v_mul_f32_e32 v36, 0xbfb8aa3b, v36
	v_exp_f32_e32 v36, v36
	v_add_co_u32_e32 v50, vcc, s89, v82
	v_add_f32_e32 v22, v22, v30
	v_add_f32_e32 v36, 1.0, v36
	v_rcp_f32_e32 v36, v36
	v_addc_co_u32_e32 v51, vcc, 0, v83, vcc
	global_load_dwordx4 v[50:53], v[50:51], off
	v_add_f32_e32 v37, v37, v45
	v_mul_f32_e32 v22, 0xbfb8aa3b, v22
	v_mul_f32_e32 v37, 0xbfb8aa3b, v37
	v_exp_f32_e32 v22, v22
	v_exp_f32_e32 v37, v37
	v_add_f32_e32 v18, v18, v26
	v_add_f32_e32 v23, v23, v31
	v_add_f32_e32 v22, 1.0, v22
	v_add_f32_e32 v37, 1.0, v37
	v_rcp_f32_e32 v22, v22
	v_rcp_f32_e32 v37, v37
	v_mul_f32_e32 v18, 0xbfb8aa3b, v18
	v_mul_f32_e32 v23, 0xbfb8aa3b, v23
	v_mul_f32_e32 v22, v22, v130
	v_exp_f32_e32 v18, v18
	v_exp_f32_e32 v23, v23
	v_add_f32_e32 v24, v24, v32
	v_add_f32_e32 v19, v19, v27
	v_add_f32_e32 v18, 1.0, v18
	v_add_f32_e32 v23, 1.0, v23
	v_rcp_f32_e32 v18, v18
	v_rcp_f32_e32 v23, v23
	v_mul_f32_e32 v24, 0xbfb8aa3b, v24
	v_mul_f32_e32 v19, 0xbfb8aa3b, v19
	v_exp_f32_e32 v24, v24
	v_mul_f32_e32 v23, v23, v131
	v_exp_f32_e32 v19, v19
	v_add_f32_e32 v25, v25, v33
	v_add_f32_e32 v24, 1.0, v24
	v_rcp_f32_e32 v24, v24
	v_add_f32_e32 v19, 1.0, v19
	v_rcp_f32_e32 v19, v19
	v_add_f32_e32 v20, v20, v28
	v_mul_f32_e32 v24, v24, v132
	v_mul_f32_e32 v25, 0xbfb8aa3b, v25
	v_mul_f32_e32 v20, 0xbfb8aa3b, v20
	v_exp_f32_e32 v25, v25
	v_exp_f32_e32 v20, v20
	v_add_f32_e32 v14, v14, v46
	v_add_f32_e32 v21, v21, v29
	v_add_f32_e32 v25, 1.0, v25
	v_add_f32_e32 v20, 1.0, v20
	v_rcp_f32_e32 v25, v25
	v_rcp_f32_e32 v20, v20
	v_mul_f32_e32 v14, 0xbfb8aa3b, v14
	v_mul_f32_e32 v21, 0xbfb8aa3b, v21
	v_mul_f32_e32 v25, v25, v133
	v_exp_f32_e32 v14, v14
	v_exp_f32_e32 v21, v21
	s_waitcnt vmcnt(0) lgkmcnt(0)
	v_lshlrev_b32_e32 v58, 16, v54
	v_and_b32_e32 v59, 0xffff0000, v54
	v_lshlrev_b32_e32 v60, 16, v55
	v_and_b32_e32 v54, 0xffff0000, v55
	v_rcp_f32_e32 v55, v34
	v_mul_f32_e32 v34, v38, v144
	v_add_f32_e32 v38, v34, v34
	v_mul_f32_e32 v38, 0x3fb8aa3b, v38
	v_exp_f32_e32 v38, v38
	v_cvt_pk_bf16_f32 v34, v34, v39
	v_add_f32_e32 v14, 1.0, v14
	v_add_f32_e32 v21, 1.0, v21
	v_sub_f32_e32 v38, 1.0, v38
	v_max_f32_e32 v38, 0, v38
	v_sqrt_f32_e32 v38, v38
	v_rcp_f32_e32 v14, v14
	v_rcp_f32_e32 v21, v21
	v_add_f32_e32 v10, v10, v42
	v_mul_f32_e32 v38, v55, v38
	v_add_f32_e32 v55, v39, v39
	v_mul_f32_e32 v55, 0x3fb8aa3b, v55
	v_exp_f32_e32 v55, v55
	v_mul_f32_e32 v38, v38, v58
	v_mul_f32_e32 v38, 0x42000000, v38
	v_mul_f32_e32 v14, v14, v144
	v_sub_f32_e32 v55, 1.0, v55
	v_max_f32_e32 v55, 0, v55
	v_sqrt_f32_e32 v55, v55
	v_mul_f32_e32 v10, 0xbfb8aa3b, v10
	v_exp_f32_e32 v10, v10
	v_add_f32_e32 v11, v11, v43
	v_mul_f32_e32 v35, v35, v55
	v_mul_f32_e32 v55, v35, v59
	v_add_f32_e32 v35, v40, v48
	v_mul_f32_e32 v35, 0xbfb8aa3b, v35
	v_exp_f32_e32 v35, v35
	v_mul_f32_e32 v39, 0x42000000, v55
	v_med3_f32 v39, v39, s29, v231
	v_add_f32_e32 v10, 1.0, v10
	v_add_f32_e32 v35, 1.0, v35
	v_rcp_f32_e32 v35, v35
	v_rcp_f32_e32 v10, v10
	v_mul_f32_e32 v11, 0xbfb8aa3b, v11
	v_exp_f32_e32 v11, v11
	v_mul_f32_e32 v35, v35, v142
	v_add_f32_e32 v40, v35, v35
	v_mul_f32_e32 v40, 0x3fb8aa3b, v40
	v_exp_f32_e32 v40, v40
	v_add_f32_e32 v11, 1.0, v11
	v_rcp_f32_e32 v11, v11
	v_add_f32_e32 v12, v12, v44
	v_sub_f32_e32 v40, 1.0, v40
	v_max_f32_e32 v40, 0, v40
	v_sqrt_f32_e32 v40, v40
	v_mul_f32_e32 v12, 0xbfb8aa3b, v12
	v_exp_f32_e32 v12, v12
	v_add_f32_e32 v6, v6, v30
	v_mul_f32_e32 v36, v36, v40
	v_add_f32_e32 v40, v41, v49
	v_mul_f32_e32 v40, 0xbfb8aa3b, v40
	v_exp_f32_e32 v40, v40
	v_mul_f32_e32 v36, v36, v60
	v_mul_f32_e32 v36, 0x42000000, v36
	v_med3_f32 v36, v36, s29, v231
	v_add_f32_e32 v40, 1.0, v40
	v_rcp_f32_e32 v40, v40
	v_add_f32_e32 v12, 1.0, v12
	v_rcp_f32_e32 v12, v12
	v_add_f32_e32 v13, v13, v45
	v_mul_f32_e32 v40, v40, v143
	v_add_f32_e32 v41, v40, v40
	v_mul_f32_e32 v41, 0x3fb8aa3b, v41
	v_exp_f32_e32 v41, v41
	v_cvt_pk_bf16_f32 v35, v35, v40
	v_med3_f32 v40, v38, s29, v231
	v_mov_b32_e32 v38, 0
	v_sub_f32_e32 v41, 1.0, v41
	v_max_f32_e32 v41, 0, v41
	v_sqrt_f32_e32 v41, v41
	v_cvt_pk_fp8_f32 v38, v40, v39
	v_lshlrev_b32_e32 v39, 16, v57
	v_and_b32_e32 v40, 0xffff0000, v57
	v_mul_f32_e32 v37, v37, v41
	v_add_f32_e32 v41, v22, v22
	v_mul_f32_e32 v41, 0x3fb8aa3b, v41
	v_exp_f32_e32 v41, v41
	v_mul_f32_e32 v37, v37, v54
	v_mul_f32_e32 v37, 0x42000000, v37
	v_med3_f32 v37, v37, s29, v231
	v_sub_f32_e32 v41, 1.0, v41
	v_max_f32_e32 v41, 0, v41
	v_sqrt_f32_e32 v41, v41
	v_cvt_pk_fp8_f32 v38, v36, v37 op_sel:[0,0,1]
	v_lshlrev_b32_e32 v36, 16, v56
	v_and_b32_e32 v37, 0xffff0000, v56
	v_mul_f32_e32 v18, v18, v41
	v_mul_f32_e32 v18, v18, v36
	v_add_f32_e32 v36, v23, v23
	v_mul_f32_e32 v36, 0x3fb8aa3b, v36
	v_exp_f32_e32 v36, v36
	v_mul_f32_e32 v18, 0x42000000, v18
	v_med3_f32 v18, v18, s29, v231
	v_mul_f32_e32 v6, 0xbfb8aa3b, v6
	v_sub_f32_e32 v36, 1.0, v36
	v_max_f32_e32 v36, 0, v36
	v_sqrt_f32_e32 v36, v36
	v_mul_f32_e32 v13, 0xbfb8aa3b, v13
	v_exp_f32_e32 v6, v6
	v_exp_f32_e32 v13, v13
	v_mul_f32_e32 v19, v19, v36
	v_add_f32_e32 v36, v24, v24
	v_mul_f32_e32 v36, 0x3fb8aa3b, v36
	v_exp_f32_e32 v36, v36
	v_mul_f32_e32 v19, v19, v37
	v_mul_f32_e32 v19, 0x42000000, v19
	v_med3_f32 v19, v19, s29, v231
	v_sub_f32_e32 v36, 1.0, v36
	v_max_f32_e32 v36, 0, v36
	v_sqrt_f32_e32 v36, v36
	v_cvt_pk_bf16_f32 v37, v24, v25
	v_add_f32_e32 v6, 1.0, v6
	v_add_f32_e32 v13, 1.0, v13
	v_mul_f32_e32 v20, v20, v36
	v_add_f32_e32 v36, v25, v25
	v_mul_f32_e32 v36, 0x3fb8aa3b, v36
	v_exp_f32_e32 v36, v36
	v_mul_f32_e32 v20, v20, v39
	v_mov_b32_e32 v39, 0
	v_cvt_pk_fp8_f32 v39, v18, v19
	v_sub_f32_e32 v36, 1.0, v36
	v_max_f32_e32 v36, 0, v36
	v_sqrt_f32_e32 v36, v36
	v_mul_f32_e32 v20, 0x42000000, v20
	v_med3_f32 v18, v20, s29, v231
	v_rcp_f32_e32 v6, v6
	v_mul_f32_e32 v21, v21, v36
	v_cvt_pk_bf16_f32 v36, v22, v23
	v_add_f32_e32 v22, v14, v14
	v_mul_f32_e32 v22, 0x3fb8aa3b, v22
	v_exp_f32_e32 v22, v22
	v_mul_f32_e32 v21, v21, v40
	v_mul_f32_e32 v21, 0x42000000, v21
	v_med3_f32 v19, v21, s29, v231
	v_sub_f32_e32 v22, 1.0, v22
	v_max_f32_e32 v22, 0, v22
	v_cvt_pk_fp8_f32 v39, v18, v19 op_sel:[0,0,1]
	v_add_co_u32_e32 v18, vcc, s92, v80
	v_sqrt_f32_e32 v22, v22
	s_nop 0
	v_addc_co_u32_e32 v19, vcc, 0, v81, vcc
	global_store_dwordx4 v[18:19], v[34:37], off
	v_add_co_u32_e32 v18, vcc, s84, v78
	v_mul_f32_e32 v10, v10, v22
	s_nop 0
	v_addc_co_u32_e32 v19, vcc, 0, v79, vcc
	global_store_dwordx2 v[18:19], v[38:39], off
	v_lshlrev_b32_e32 v18, 16, v50
	v_mul_f32_e32 v18, v10, v18
	v_add_f32_e32 v10, v15, v47
	v_mul_f32_e32 v10, 0xbfb8aa3b, v10
	v_exp_f32_e32 v10, v10
	v_and_b32_e32 v19, 0xffff0000, v50
	v_rcp_f32_e32 v13, v13
	v_mul_f32_e32 v6, v6, v130
	v_add_f32_e32 v10, 1.0, v10
	v_rcp_f32_e32 v10, v10
	v_add_f32_e32 v2, v2, v26
	v_add_f32_e32 v7, v7, v31
	v_mul_f32_e32 v2, 0xbfb8aa3b, v2
	v_mul_f32_e32 v10, v10, v145
	v_add_f32_e32 v15, v10, v10
	v_mul_f32_e32 v15, 0x3fb8aa3b, v15
	v_exp_f32_e32 v15, v15
	v_mul_f32_e32 v7, 0xbfb8aa3b, v7
	v_exp_f32_e32 v2, v2
	v_exp_f32_e32 v7, v7
	v_sub_f32_e32 v15, 1.0, v15
	v_max_f32_e32 v15, 0, v15
	v_sqrt_f32_e32 v15, v15
	v_cvt_pk_bf16_f32 v10, v14, v10
	v_mul_f32_e32 v14, 0x42000000, v18
	v_add_f32_e32 v2, 1.0, v2
	v_mul_f32_e32 v11, v11, v15
	v_mul_f32_e32 v15, v11, v19
	v_add_f32_e32 v11, v16, v48
	v_mul_f32_e32 v11, 0xbfb8aa3b, v11
	v_exp_f32_e32 v11, v11
	v_mul_f32_e32 v15, 0x42000000, v15
	v_med3_f32 v15, v15, s29, v231
	v_add_f32_e32 v7, 1.0, v7
	v_add_f32_e32 v11, 1.0, v11
	v_rcp_f32_e32 v11, v11
	v_lshlrev_b32_e32 v20, 16, v51
	v_and_b32_e32 v21, 0xffff0000, v51
	v_rcp_f32_e32 v2, v2
	v_mul_f32_e32 v11, v11, v142
	v_add_f32_e32 v16, v11, v11
	v_mul_f32_e32 v16, 0x3fb8aa3b, v16
	v_exp_f32_e32 v16, v16
	v_rcp_f32_e32 v7, v7
	v_add_f32_e32 v8, v8, v32
	v_add_f32_e32 v3, v3, v27
	v_sub_f32_e32 v16, 1.0, v16
	v_max_f32_e32 v16, 0, v16
	v_sqrt_f32_e32 v16, v16
	v_mul_f32_e32 v7, v7, v131
	v_mul_f32_e32 v8, 0xbfb8aa3b, v8
	v_mul_f32_e32 v3, 0xbfb8aa3b, v3
	v_mul_f32_e32 v12, v12, v16
	v_add_f32_e32 v16, v17, v49
	v_mul_f32_e32 v16, 0xbfb8aa3b, v16
	v_exp_f32_e32 v16, v16
	v_mul_f32_e32 v12, v12, v20
	v_mul_f32_e32 v12, 0x42000000, v12
	v_med3_f32 v12, v12, s29, v231
	v_add_f32_e32 v16, 1.0, v16
	v_rcp_f32_e32 v16, v16
	v_exp_f32_e32 v8, v8
	v_exp_f32_e32 v3, v3
	v_add_f32_e32 v9, v9, v33
	v_mul_f32_e32 v16, v16, v143
	v_add_f32_e32 v17, v16, v16
	v_mul_f32_e32 v17, 0x3fb8aa3b, v17
	v_exp_f32_e32 v17, v17
	v_cvt_pk_bf16_f32 v11, v11, v16
	v_med3_f32 v16, v14, s29, v231
	v_mov_b32_e32 v14, 0
	v_sub_f32_e32 v17, 1.0, v17
	v_max_f32_e32 v17, 0, v17
	v_sqrt_f32_e32 v17, v17
	v_cvt_pk_fp8_f32 v14, v16, v15
	v_add_f32_e32 v8, 1.0, v8
	v_add_f32_e32 v3, 1.0, v3
	v_mul_f32_e32 v13, v13, v17
	v_add_f32_e32 v17, v6, v6
	v_mul_f32_e32 v17, 0x3fb8aa3b, v17
	v_exp_f32_e32 v17, v17
	v_mul_f32_e32 v13, v13, v21
	v_mul_f32_e32 v13, 0x42000000, v13
	v_med3_f32 v13, v13, s29, v231
	v_sub_f32_e32 v17, 1.0, v17
	v_max_f32_e32 v17, 0, v17
	v_sqrt_f32_e32 v17, v17
	v_cvt_pk_fp8_f32 v14, v12, v13 op_sel:[0,0,1]
	v_lshlrev_b32_e32 v12, 16, v52
	v_rcp_f32_e32 v8, v8
	v_mul_f32_e32 v2, v2, v17
	v_mul_f32_e32 v2, v2, v12
	v_add_f32_e32 v12, v7, v7
	v_mul_f32_e32 v12, 0x3fb8aa3b, v12
	v_exp_f32_e32 v12, v12
	v_rcp_f32_e32 v3, v3
	v_mul_f32_e32 v8, v8, v132
	v_add_f32_e32 v4, v4, v28
	v_sub_f32_e32 v12, 1.0, v12
	v_max_f32_e32 v12, 0, v12
	v_sqrt_f32_e32 v12, v12
	v_mul_f32_e32 v9, 0xbfb8aa3b, v9
	v_mul_f32_e32 v4, 0xbfb8aa3b, v4
	v_exp_f32_e32 v9, v9
	v_mul_f32_e32 v3, v3, v12
	v_add_f32_e32 v12, v8, v8
	v_mul_f32_e32 v12, 0x3fb8aa3b, v12
	v_exp_f32_e32 v12, v12
	v_exp_f32_e32 v4, v4
	v_add_f32_e32 v9, 1.0, v9
	v_rcp_f32_e32 v9, v9
	v_sub_f32_e32 v12, 1.0, v12
	v_add_f32_e32 v4, 1.0, v4
	v_max_f32_e32 v12, 0, v12
	v_rcp_f32_e32 v4, v4
	v_sqrt_f32_e32 v12, v12
	v_mul_f32_e32 v9, v9, v133
	v_add_f32_e32 v5, v5, v29
	v_mul_f32_e32 v5, 0xbfb8aa3b, v5
	v_mul_f32_e32 v4, v4, v12
	v_add_f32_e32 v12, v9, v9
	v_mul_f32_e32 v12, 0x3fb8aa3b, v12
	v_exp_f32_e32 v12, v12
	v_exp_f32_e32 v5, v5
	v_and_b32_e32 v13, 0xffff0000, v52
	v_mul_f32_e32 v3, v3, v13
	v_sub_f32_e32 v12, 1.0, v12
	v_add_f32_e32 v5, 1.0, v5
	v_max_f32_e32 v12, 0, v12
	v_rcp_f32_e32 v5, v5
	v_sqrt_f32_e32 v12, v12
	v_lshlrev_b32_e32 v15, 16, v53
	v_mul_f32_e32 v2, 0x42000000, v2
	v_mul_f32_e32 v3, 0x42000000, v3
	v_mul_f32_e32 v4, v4, v15
	v_med3_f32 v2, v2, s29, v231
	v_med3_f32 v3, v3, s29, v231
	v_mov_b32_e32 v15, 0
	v_and_b32_e32 v16, 0xffff0000, v53
	v_mul_f32_e32 v5, v5, v12
	v_cvt_pk_fp8_f32 v15, v2, v3
	v_mul_f32_e32 v5, v5, v16
	v_mul_f32_e32 v4, 0x42000000, v4
	v_mul_f32_e32 v5, 0x42000000, v5
	v_med3_f32 v2, v4, s29, v231
	v_med3_f32 v3, v5, s29, v231
	v_cvt_pk_fp8_f32 v15, v2, v3 op_sel:[0,0,1]
	v_add_co_u32_e32 v2, vcc, 0x18000, v80
	v_cvt_pk_bf16_f32 v12, v6, v7
	v_cvt_pk_bf16_f32 v13, v8, v9
	v_addc_co_u32_e32 v3, vcc, 0, v81, vcc
	global_store_dwordx4 v[2:3], v[10:13], off
	v_add_co_u32_e32 v2, vcc, 0xc000, v78
	s_nop 1
	v_addc_co_u32_e32 v3, vcc, 0, v79, vcc
	global_store_dwordx2 v[2:3], v[14:15], off
	s_and_b64 vcc, exec, s[12:13]
	s_mov_b32 s82, s40
	s_mov_b32 s52, s42
	s_mov_b64 s[14:15], s[46:47]
	s_mov_b64 s[48:49], s[44:45]
	s_mov_b32 s94, s23
	s_cbranch_vccz .LBB0_1638
	s_waitcnt vmcnt(0)
	s_cmpk_gt_u32 s22, 0xff
	v_readlane_b32 s81, v253, 46
	v_readlane_b32 s80, v253, 45
	v_readlane_b32 s89, v253, 44
	s_cbranch_scc1 .LBB0_1649
	s_barrier

.LBB0_1705:
	s_lshl_b32 s0, s52, 5
	s_and_b32 s0, s0, 0xe0
	s_ashr_i32 s1, s52, 3
	s_add_i32 s0, s0, s1
	s_lshl_b32 s0, s0, 18
	s_and_b32 s0, s0, 0x7fe00000
	s_waitcnt vmcnt(0)
	v_add_u32_e32 v2, s0, v168
	s_lshl_b32 s0, s1, 7
	s_and_b32 s0, s0, 0x380
	v_or_b32_e32 v2, s0, v2
	v_or_b32_e32 v3, v2, v169
	v_lshlrev_b32_e32 v68, 1, v3
	v_or_b32_e32 v66, 0x800, v68
	v_lshl_add_u64 v[80:81], s[18:19], 0, v[66:67]
	v_or_b32_e32 v66, 0x1000, v68
	v_mov_b32_e32 v69, v67
	s_mov_b32 s4, 0x7fff03f8
	v_lshl_add_u64 v[82:83], s[18:19], 0, v[66:67]
	v_or_b32_e32 v66, 0x1800, v68
	v_lshl_add_u64 v[78:79], s[18:19], 0, v[68:69]
	v_bitop3_b32 v70, v2, s4, v169 bitop3:0xc8
	v_mov_b32_e32 v71, v67
	v_lshl_add_u64 v[84:85], s[18:19], 0, v[66:67]
	v_lshl_add_u64 v[76:77], s[24:25], 0, v[70:71]
	global_load_dwordx4 v[30:33], v[78:79], off
	global_load_dwordx2 v[86:87], v[76:77], off
	global_load_dwordx4 v[26:29], v[80:81], off
	global_load_dwordx4 v[22:25], v[82:83], off
	global_load_dwordx4 v[18:21], v[84:85], off
	global_load_dwordx2 v[92:93], v[76:77], off offset:1024
	global_load_dwordx2 v[94:95], v[76:77], off offset:2048
	global_load_dwordx2 v[96:97], v[76:77], off offset:3072
	s_lshl_b32 s4, s50, 18
	s_and_b32 s4, s4, 0x3800000
	s_lshl_b32 s1, s1, 18
	s_add_i32 s4, s4, s1
	s_and_b32 s1, s4, 0x7fe00000
	s_or_b32 s0, s0, s1
	v_add_u32_e32 v2, s0, v172
	v_and_b32_e32 v72, 0x7ffffff8, v2
	v_mov_b32_e32 v73, v67
	v_lshl_add_u64 v[74:75], s[36:37], 0, v[72:73]
	v_lshlrev_b32_e32 v69, 1, v2
	v_add_u32_e32 v88, 0x3800, v69
	v_mov_b64_e32 v[90:91], v[74:75]
	s_mov_b32 s4, 8
	s_mov_b32 s6, 0
	v_mov_b32_e32 v10, v67
	v_mov_b32_e32 v11, v67
	v_mov_b32_e32 v12, v67
	v_mov_b32_e32 v13, v67
	v_mov_b32_e32 v6, v67
	v_mov_b32_e32 v7, v67
	v_mov_b32_e32 v8, v67
	v_mov_b32_e32 v9, v67
	v_mov_b32_e32 v4, v67
	v_mov_b32_e32 v5, v67
	v_mov_b32_e32 v2, v67
	v_mov_b32_e32 v3, v67
	v_mov_b32_e32 v16, v67
	v_mov_b32_e32 v17, v67
	v_mov_b32_e32 v14, v67
	v_mov_b32_e32 v15, v67
.LBB0_1706:
	v_add_u32_e32 v66, 0xffffe800, v88
	v_lshl_add_u64 v[34:35], s[18:19], 0, v[66:67]
	v_add_u32_e32 v66, 0xfffff000, v88
	v_lshl_add_u64 v[36:37], s[18:19], 0, v[66:67]
	v_add_u32_e32 v66, 0xfffff800, v88
	global_load_dwordx4 v[58:61], v[34:35], off
	global_load_dwordx4 v[54:57], v[36:37], off
	v_lshl_add_u64 v[34:35], s[18:19], 0, v[66:67]
	v_mov_b32_e32 v89, v67
	v_lshl_add_u64 v[36:37], s[18:19], 0, v[88:89]
	global_load_dwordx4 v[50:53], v[34:35], off
	global_load_dwordx4 v[42:45], v[36:37], off
	global_load_dwordx2 v[106:107], v[90:91], off
	global_load_dwordx2 v[108:109], v[90:91], off offset:1024
	global_load_dwordx2 v[110:111], v[90:91], off offset:2048
	global_load_dwordx2 v[112:113], v[90:91], off offset:3072
	s_add_i32 s5, s6, 2
	s_cmp_lt_u32 s6, 14
	s_cselect_b64 s[0:1], -1, 0
	s_and_b64 vcc, s[0:1], exec
	s_cselect_b32 s0, s4, 60
	v_lshl_add_u32 v66, s0, 11, v68
	v_lshl_add_u64 v[34:35], s[18:19], 0, v[66:67]
	v_lshl_add_u32 v66, s0, 10, v70
	s_or_b32 s1, s0, 1
	v_lshl_add_u64 v[38:39], s[24:25], 0, v[66:67]
	v_lshl_add_u32 v66, s1, 11, v68
	s_waitcnt vmcnt(0) lgkmcnt(0)
	v_cvt_pk_f32_fp8_e32 v[150:151], v86
	v_cvt_pk_f32_fp8_sdwa v[134:135], v86 src0_sel:WORD_1
	v_cvt_pk_f32_fp8_e32 v[118:119], v87
	v_cvt_pk_f32_fp8_sdwa v[102:103], v87 src0_sel:WORD_1
	global_load_dwordx4 v[34:37], v[34:35], off
	v_cvt_pk_f32_fp8_e32 v[152:153], v92
	global_load_dwordx2 v[86:87], v[38:39], off
	v_lshl_add_u64 v[38:39], s[18:19], 0, v[66:67]
	v_lshl_add_u32 v66, s1, 10, v70
	s_or_b32 s1, s0, 2
	v_lshl_add_u64 v[46:47], s[24:25], 0, v[66:67]
	v_lshl_add_u32 v66, s1, 11, v68
	v_cvt_pk_f32_fp8_sdwa v[136:137], v92 src0_sel:WORD_1
	v_cvt_pk_f32_fp8_e32 v[120:121], v93
	v_cvt_pk_f32_fp8_sdwa v[104:105], v93 src0_sel:WORD_1
	global_load_dwordx4 v[38:41], v[38:39], off
	s_or_b32 s0, s0, 3
	global_load_dwordx2 v[92:93], v[46:47], off
	v_lshl_add_u64 v[46:47], s[18:19], 0, v[66:67]
	v_lshl_add_u32 v66, s1, 10, v70
	v_lshl_add_u64 v[62:63], s[24:25], 0, v[66:67]
	v_lshl_add_u32 v66, s0, 11, v68
	v_cvt_pk_f32_fp8_e32 v[146:147], v94
	v_cvt_pk_f32_fp8_sdwa v[130:131], v94 src0_sel:WORD_1
	v_cvt_pk_f32_fp8_e32 v[114:115], v95
	v_cvt_pk_f32_fp8_sdwa v[98:99], v95 src0_sel:WORD_1
	global_load_dwordx4 v[46:49], v[46:47], off
	v_cvt_pk_f32_fp8_e32 v[148:149], v96
	global_load_dwordx2 v[94:95], v[62:63], off
	v_lshl_add_u64 v[62:63], s[18:19], 0, v[66:67]
	v_lshl_add_u32 v66, s0, 10, v70
	v_cvt_pk_f32_fp8_sdwa v[132:133], v96 src0_sel:WORD_1
	v_cvt_pk_f32_fp8_e32 v[116:117], v97
	v_cvt_pk_f32_fp8_sdwa v[100:101], v97 src0_sel:WORD_1
	v_lshl_add_u64 v[96:97], s[24:25], 0, v[66:67]
	global_load_dwordx4 v[62:65], v[62:63], off
	s_nop 0
	global_load_dwordx2 v[96:97], v[96:97], off
	v_lshlrev_b32_e32 v162, 16, v30
	v_and_b32_e32 v163, 0xffff0000, v30
	v_mul_f32_e32 v30, 0x3fb8aa3b, v162
	v_exp_f32_e32 v164, v30
	v_mul_f32_e32 v30, 0x3fb8aa3b, v163
	v_pk_add_f32 v[10:11], v[10:11], v[162:163]
	v_lshlrev_b32_e32 v162, 16, v26
	v_exp_f32_e32 v165, v30
	v_and_b32_e32 v163, 0xffff0000, v26
	v_mul_f32_e32 v26, 0x3fb8aa3b, v162
	v_exp_f32_e32 v176, v26
	v_mul_f32_e32 v26, 0x3fb8aa3b, v163
	v_exp_f32_e32 v177, v26
	v_pk_add_f32 v[10:11], v[10:11], v[162:163]
	v_lshlrev_b32_e32 v162, 16, v22
	v_and_b32_e32 v163, 0xffff0000, v22
	v_pk_fma_f32 v[14:15], v[14:15], v[164:165], v[150:151]
	v_lshlrev_b32_e32 v150, 16, v18
	v_pk_add_f32 v[10:11], v[10:11], v[162:163]
	v_and_b32_e32 v151, 0xffff0000, v18
	v_mul_f32_e32 v18, 0x3fb8aa3b, v150
	v_pk_fma_f32 v[14:15], v[176:177], v[14:15], v[152:153]
	v_exp_f32_e32 v152, v18
	v_mul_f32_e32 v18, 0x3fb8aa3b, v151
	v_pk_add_f32 v[10:11], v[10:11], v[150:151]
	v_lshlrev_b32_e32 v150, 16, v58
	v_exp_f32_e32 v153, v18
	v_and_b32_e32 v151, 0xffff0000, v58
	v_mul_f32_e32 v18, 0x3fb8aa3b, v150
	v_mul_f32_e32 v22, 0x3fb8aa3b, v162
	v_exp_f32_e32 v162, v18
	v_mul_f32_e32 v18, 0x3fb8aa3b, v151
	v_pk_add_f32 v[10:11], v[10:11], v[150:151]
	v_lshlrev_b32_e32 v150, 16, v54
	v_exp_f32_e32 v178, v22
	v_mul_f32_e32 v22, 0x3fb8aa3b, v163
	v_exp_f32_e32 v163, v18
	v_and_b32_e32 v151, 0xffff0000, v54
	v_mul_f32_e32 v18, 0x3fb8aa3b, v150
	v_exp_f32_e32 v164, v18
	v_mul_f32_e32 v18, 0x3fb8aa3b, v151
	v_pk_add_f32 v[10:11], v[10:11], v[150:151]
	v_lshlrev_b32_e32 v150, 16, v50
	v_exp_f32_e32 v165, v18
	v_and_b32_e32 v151, 0xffff0000, v50
	v_mul_f32_e32 v18, 0x3fb8aa3b, v150
	v_exp_f32_e32 v179, v22
	v_exp_f32_e32 v176, v18
	v_mul_f32_e32 v18, 0x3fb8aa3b, v151
	v_pk_add_f32 v[10:11], v[10:11], v[150:151]
	v_lshlrev_b32_e32 v150, 16, v42
	v_exp_f32_e32 v177, v18
	v_and_b32_e32 v151, 0xffff0000, v42
	v_mul_f32_e32 v18, 0x3fb8aa3b, v150
	v_exp_f32_e32 v180, v18
	v_mul_f32_e32 v18, 0x3fb8aa3b, v151
	v_lshlrev_b32_e32 v30, 16, v31
	v_exp_f32_e32 v181, v18
	v_and_b32_e32 v31, 0xffff0000, v31
	v_mul_f32_e32 v18, 0x3fb8aa3b, v30
	v_pk_fma_f32 v[14:15], v[178:179], v[14:15], v[146:147]
	v_exp_f32_e32 v146, v18
	v_mul_f32_e32 v18, 0x3fb8aa3b, v31
	v_lshlrev_b32_e32 v26, 16, v27
	v_exp_f32_e32 v147, v18
	v_and_b32_e32 v27, 0xffff0000, v27
	v_mul_f32_e32 v18, 0x3fb8aa3b, v26
	v_pk_add_f32 v[12:13], v[12:13], v[30:31]
	v_exp_f32_e32 v30, v18
	v_mul_f32_e32 v18, 0x3fb8aa3b, v27
	v_lshlrev_b32_e32 v22, 16, v23
	v_exp_f32_e32 v31, v18
	v_and_b32_e32 v23, 0xffff0000, v23
	v_mul_f32_e32 v18, 0x3fb8aa3b, v22
	v_pk_add_f32 v[12:13], v[12:13], v[26:27]
	v_exp_f32_e32 v26, v18
	v_mul_f32_e32 v18, 0x3fb8aa3b, v23
	v_exp_f32_e32 v27, v18
	v_pk_add_f32 v[12:13], v[12:13], v[22:23]
	v_lshlrev_b32_e32 v18, 16, v19
	v_and_b32_e32 v19, 0xffff0000, v19
	v_pk_fma_f32 v[16:17], v[16:17], v[146:147], v[134:135]
	v_mul_f32_e32 v22, 0x3fb8aa3b, v18
	v_mul_f32_e32 v23, 0x3fb8aa3b, v19
	v_pk_add_f32 v[12:13], v[12:13], v[18:19]
	v_lshlrev_b32_e32 v18, 16, v59
	v_and_b32_e32 v19, 0xffff0000, v59
	v_pk_fma_f32 v[16:17], v[30:31], v[16:17], v[136:137]
	v_mul_f32_e32 v30, 0x3fb8aa3b, v18
	v_pk_add_f32 v[12:13], v[12:13], v[18:19]
	v_lshlrev_b32_e32 v18, 16, v55
	v_mul_f32_e32 v31, 0x3fb8aa3b, v19
	v_and_b32_e32 v19, 0xffff0000, v55
	v_mul_f32_e32 v42, 0x3fb8aa3b, v18
	v_exp_f32_e32 v22, v22
	v_exp_f32_e32 v23, v23
	v_exp_f32_e32 v54, v42
	v_mul_f32_e32 v42, 0x3fb8aa3b, v19
	v_pk_add_f32 v[12:13], v[12:13], v[18:19]
	v_lshlrev_b32_e32 v18, 16, v51
	v_exp_f32_e32 v55, v42
	v_and_b32_e32 v19, 0xffff0000, v51
	v_mul_f32_e32 v42, 0x3fb8aa3b, v18
	v_exp_f32_e32 v50, v42
	v_mul_f32_e32 v42, 0x3fb8aa3b, v19
	v_pk_add_f32 v[12:13], v[12:13], v[18:19]
	v_lshlrev_b32_e32 v18, 16, v43
	v_and_b32_e32 v19, 0xffff0000, v43
	v_exp_f32_e32 v51, v42
	v_mul_f32_e32 v42, 0x3fb8aa3b, v18
	v_mul_f32_e32 v43, 0x3fb8aa3b, v19
	v_pk_fma_f32 v[16:17], v[26:27], v[16:17], v[130:131]
	v_pk_add_f32 v[12:13], v[12:13], v[18:19]
	v_lshlrev_b32_e32 v18, 16, v32
	v_and_b32_e32 v19, 0xffff0000, v32
	v_cvt_pk_f32_fp8_sdwa v[138:139], v106 src0_sel:WORD_1
	v_exp_f32_e32 v30, v30
	v_exp_f32_e32 v31, v31
	v_pk_fma_f32 v[16:17], v[22:23], v[16:17], v[132:133]
	v_mul_f32_e32 v22, 0x3fb8aa3b, v18
	v_mul_f32_e32 v23, 0x3fb8aa3b, v19
	v_exp_f32_e32 v22, v22
	v_exp_f32_e32 v23, v23
	v_pk_add_f32 v[6:7], v[6:7], v[18:19]
	v_lshlrev_b32_e32 v18, 16, v28
	v_and_b32_e32 v19, 0xffff0000, v28
	v_mul_f32_e32 v26, 0x3fb8aa3b, v18
	v_mul_f32_e32 v27, 0x3fb8aa3b, v19
	v_pk_add_f32 v[6:7], v[6:7], v[18:19]
	v_lshlrev_b32_e32 v18, 16, v24
	v_and_b32_e32 v19, 0xffff0000, v24
	v_cvt_pk_f32_fp8_sdwa v[140:141], v108 src0_sel:WORD_1
	v_exp_f32_e32 v26, v26
	v_exp_f32_e32 v27, v27
	v_mul_f32_e32 v24, 0x3fb8aa3b, v18
	v_pk_add_f32 v[6:7], v[6:7], v[18:19]
	v_lshlrev_b32_e32 v18, 16, v20
	v_cvt_pk_f32_fp8_sdwa v[142:143], v110 src0_sel:WORD_1
	v_pk_fma_f32 v[16:17], v[30:31], v[16:17], v[138:139]
	v_exp_f32_e32 v30, v24
	v_mul_f32_e32 v24, 0x3fb8aa3b, v19
	v_and_b32_e32 v19, 0xffff0000, v20
	v_mul_f32_e32 v20, 0x3fb8aa3b, v18
	v_cvt_pk_f32_fp8_sdwa v[144:145], v112 src0_sel:WORD_1
	v_exp_f32_e32 v42, v42
	v_exp_f32_e32 v43, v43
	v_pk_fma_f32 v[2:3], v[2:3], v[22:23], v[118:119]
	v_exp_f32_e32 v22, v20
	v_mul_f32_e32 v20, 0x3fb8aa3b, v19
	v_pk_add_f32 v[6:7], v[6:7], v[18:19]
	v_lshlrev_b32_e32 v18, 16, v60
	v_exp_f32_e32 v23, v20
	v_and_b32_e32 v19, 0xffff0000, v60
	v_mul_f32_e32 v20, 0x3fb8aa3b, v18
	v_pk_fma_f32 v[16:17], v[54:55], v[16:17], v[140:141]
	v_pk_fma_f32 v[2:3], v[26:27], v[2:3], v[120:121]
	v_exp_f32_e32 v26, v20
	v_mul_f32_e32 v20, 0x3fb8aa3b, v19
	v_pk_add_f32 v[6:7], v[6:7], v[18:19]
	v_lshlrev_b32_e32 v18, 16, v56
	v_pk_fma_f32 v[16:17], v[50:51], v[16:17], v[142:143]
	v_exp_f32_e32 v27, v20
	v_and_b32_e32 v19, 0xffff0000, v56
	v_mul_f32_e32 v20, 0x3fb8aa3b, v18
	v_pk_fma_f32 v[16:17], v[42:43], v[16:17], v[144:145]
	v_exp_f32_e32 v42, v20
	v_mul_f32_e32 v20, 0x3fb8aa3b, v19
	v_pk_add_f32 v[6:7], v[6:7], v[18:19]
	v_lshlrev_b32_e32 v18, 16, v52
	v_exp_f32_e32 v31, v24
	v_exp_f32_e32 v43, v20
	v_and_b32_e32 v19, 0xffff0000, v52
	v_mul_f32_e32 v20, 0x3fb8aa3b, v18
	v_exp_f32_e32 v50, v20
	v_mul_f32_e32 v20, 0x3fb8aa3b, v19
	v_pk_add_f32 v[6:7], v[6:7], v[18:19]
	v_lshlrev_b32_e32 v18, 16, v44
	v_exp_f32_e32 v51, v20
	v_and_b32_e32 v19, 0xffff0000, v44
	v_mul_f32_e32 v20, 0x3fb8aa3b, v18
	v_cvt_pk_f32_fp8_e32 v[122:123], v107
	v_exp_f32_e32 v54, v20
	v_mul_f32_e32 v20, 0x3fb8aa3b, v19
	v_pk_add_f32 v[6:7], v[6:7], v[18:19]
	v_lshlrev_b32_e32 v18, 16, v33
	v_exp_f32_e32 v55, v20
	v_pk_fma_f32 v[2:3], v[30:31], v[2:3], v[114:115]
	v_and_b32_e32 v19, 0xffff0000, v33
	v_mul_f32_e32 v20, 0x3fb8aa3b, v18
	v_pk_fma_f32 v[2:3], v[22:23], v[2:3], v[116:117]
	v_exp_f32_e32 v22, v20
	v_mul_f32_e32 v20, 0x3fb8aa3b, v19
	v_pk_add_f32 v[8:9], v[8:9], v[18:19]
	v_lshlrev_b32_e32 v18, 16, v29
	v_exp_f32_e32 v23, v20
	v_and_b32_e32 v19, 0xffff0000, v29
	v_mul_f32_e32 v20, 0x3fb8aa3b, v18
	v_pk_fma_f32 v[2:3], v[26:27], v[2:3], v[122:123]
	v_exp_f32_e32 v26, v20
	v_mul_f32_e32 v20, 0x3fb8aa3b, v19
	v_pk_add_f32 v[8:9], v[8:9], v[18:19]
	v_lshlrev_b32_e32 v18, 16, v25
	v_exp_f32_e32 v27, v20
	v_and_b32_e32 v19, 0xffff0000, v25
	v_mul_f32_e32 v20, 0x3fb8aa3b, v18
	v_exp_f32_e32 v24, v20
	v_mul_f32_e32 v20, 0x3fb8aa3b, v19
	v_pk_add_f32 v[8:9], v[8:9], v[18:19]
	v_lshlrev_b32_e32 v18, 16, v21
	v_and_b32_e32 v19, 0xffff0000, v21
	v_exp_f32_e32 v25, v20
	v_mul_f32_e32 v20, 0x3fb8aa3b, v18
	v_mul_f32_e32 v21, 0x3fb8aa3b, v19
	v_pk_add_f32 v[8:9], v[8:9], v[18:19]
	v_lshlrev_b32_e32 v18, 16, v61
	v_and_b32_e32 v19, 0xffff0000, v61
	v_pk_fma_f32 v[4:5], v[4:5], v[22:23], v[102:103]
	v_exp_f32_e32 v20, v20
	v_exp_f32_e32 v21, v21
	v_mul_f32_e32 v22, 0x3fb8aa3b, v18
	v_mul_f32_e32 v23, 0x3fb8aa3b, v19
	v_pk_add_f32 v[8:9], v[8:9], v[18:19]
	v_lshlrev_b32_e32 v18, 16, v57
	v_and_b32_e32 v19, 0xffff0000, v57
	v_cvt_pk_f32_fp8_e32 v[154:155], v106
	v_cvt_pk_f32_fp8_sdwa v[106:107], v107 src0_sel:WORD_1
	v_pk_fma_f32 v[4:5], v[26:27], v[4:5], v[104:105]
	v_exp_f32_e32 v22, v22
	v_exp_f32_e32 v23, v23
	v_mul_f32_e32 v26, 0x3fb8aa3b, v18
	v_mul_f32_e32 v27, 0x3fb8aa3b, v19
	v_pk_add_f32 v[8:9], v[8:9], v[18:19]
	v_lshlrev_b32_e32 v18, 16, v53
	v_and_b32_e32 v19, 0xffff0000, v53
	v_cvt_pk_f32_fp8_e32 v[156:157], v108
	v_cvt_pk_f32_fp8_e32 v[124:125], v109
	v_cvt_pk_f32_fp8_sdwa v[108:109], v109 src0_sel:WORD_1
	v_exp_f32_e32 v26, v26
	v_exp_f32_e32 v27, v27
	v_mul_f32_e32 v28, 0x3fb8aa3b, v18
	v_mul_f32_e32 v29, 0x3fb8aa3b, v19
	v_pk_add_f32 v[8:9], v[8:9], v[18:19]
	v_lshlrev_b32_e32 v18, 16, v45
	v_and_b32_e32 v19, 0xffff0000, v45
	v_cvt_pk_f32_fp8_e32 v[158:159], v110
	v_cvt_pk_f32_fp8_e32 v[126:127], v111
	v_cvt_pk_f32_fp8_sdwa v[110:111], v111 src0_sel:WORD_1
	v_exp_f32_e32 v28, v28
	v_exp_f32_e32 v29, v29
	v_mul_f32_e32 v30, 0x3fb8aa3b, v18
	v_mul_f32_e32 v31, 0x3fb8aa3b, v19
	v_pk_fma_f32 v[4:5], v[24:25], v[4:5], v[98:99]
	v_cvt_pk_f32_fp8_e32 v[160:161], v112
	v_cvt_pk_f32_fp8_e32 v[128:129], v113
	v_cvt_pk_f32_fp8_sdwa v[112:113], v113 src0_sel:WORD_1
	v_exp_f32_e32 v30, v30
	v_exp_f32_e32 v31, v31
	v_pk_fma_f32 v[4:5], v[20:21], v[4:5], v[100:101]
	v_pk_fma_f32 v[14:15], v[152:153], v[14:15], v[148:149]
	v_pk_fma_f32 v[4:5], v[22:23], v[4:5], v[106:107]
	v_pk_fma_f32 v[14:15], v[162:163], v[14:15], v[154:155]
	v_pk_fma_f32 v[4:5], v[26:27], v[4:5], v[108:109]
	v_pk_fma_f32 v[14:15], v[164:165], v[14:15], v[156:157]
	v_pk_fma_f32 v[2:3], v[42:43], v[2:3], v[124:125]
	v_pk_fma_f32 v[4:5], v[28:29], v[4:5], v[110:111]
	v_pk_fma_f32 v[14:15], v[176:177], v[14:15], v[158:159]
	v_pk_fma_f32 v[2:3], v[50:51], v[2:3], v[126:127]
	v_pk_fma_f32 v[4:5], v[30:31], v[4:5], v[112:113]
	v_pk_add_f32 v[8:9], v[8:9], v[18:19]
	s_waitcnt vmcnt(0) lgkmcnt(0)
	v_mov_b64_e32 v[18:19], v[62:63]
	v_mov_b64_e32 v[22:23], v[46:47]
	v_mov_b64_e32 v[26:27], v[38:39]
	v_mov_b64_e32 v[30:31], v[34:35]
	v_pk_fma_f32 v[14:15], v[180:181], v[14:15], v[160:161]
	v_pk_add_f32 v[10:11], v[10:11], v[150:151]
	v_pk_fma_f32 v[2:3], v[54:55], v[2:3], v[128:129]
	s_add_i32 s4, s4, 8
	v_lshl_add_u64 v[90:91], v[90:91], 0, s[40:41]
	v_add_u32_e32 v88, 0x4000, v88
	s_mov_b32 s6, s5
	v_mov_b64_e32 v[20:21], v[64:65]
	v_mov_b64_e32 v[24:25], v[48:49]
	v_mov_b64_e32 v[28:29], v[40:41]
	v_mov_b64_e32 v[32:33], v[36:37]
	s_cbranch_vccnz .LBB0_1706
	ds_write_b128 v170, v[10:13]
	ds_write_b128 v170, v[6:9] offset:16
	ds_write_b128 v170, v[14:17] offset:16384
	ds_write_b128 v170, v[2:5] offset:16400
	v_or_b32_e32 v86, 0x1f800, v68
	v_mov_b32_e32 v87, v67
	v_lshl_add_u64 v[2:3], s[28:29], 0, v[70:71]
	s_mov_b32 s0, 0xf000
	v_or_b32_e32 v66, 0x1e800, v68
	v_lshl_add_u64 v[88:89], s[20:21], 0, v[86:87]
	v_add_co_u32_e32 v4, vcc, s0, v2
	v_or_b32_e32 v90, 0x1f000, v68
	v_mov_b32_e32 v91, v67
	v_lshl_add_u64 v[6:7], s[20:21], 0, v[66:67]
	v_or_b32_e32 v66, 0x1e000, v68
	v_addc_co_u32_e32 v5, vcc, 0, v3, vcc
	v_lshl_add_u64 v[92:93], s[20:21], 0, v[90:91]
	global_load_dwordx4 v[30:33], v[88:89], off
	global_load_dwordx4 v[26:29], v[92:93], off
	v_lshl_add_u64 v[8:9], s[20:21], 0, v[66:67]
	global_load_dwordx4 v[22:25], v[6:7], off
	global_load_dwordx4 v[18:21], v[8:9], off
	global_load_dwordx2 v[102:103], v[4:5], off offset:3072
	global_load_dwordx2 v[104:105], v[4:5], off offset:2048
	global_load_dwordx2 v[106:107], v[4:5], off offset:1024
	global_load_dwordx2 v[108:109], v[4:5], off
	s_mov_b64 s[0:1], 0xfc00
	v_lshl_add_u64 v[96:97], v[2:3], 0, s[0:1]
	s_mov_b64 s[0:1], 0xf800
	v_lshl_add_u64 v[94:95], v[2:3], 0, s[0:1]
	v_mov_b32_e32 v2, 0
	s_mov_b32 s6, 0
	v_lshl_add_u64 v[98:99], s[38:39], 0, v[72:73]
	v_add_u32_e32 v100, 0x1c000, v69
	s_mov_b32 s4, 8
	v_mov_b32_e32 v3, v2
	v_mov_b32_e32 v4, v2
	v_mov_b32_e32 v5, v2
	v_mov_b32_e32 v10, v2
	v_mov_b32_e32 v11, v2
	v_mov_b32_e32 v12, v2
	v_mov_b32_e32 v13, v2
	v_mov_b32_e32 v8, v2
	v_mov_b32_e32 v9, v2
	v_mov_b32_e32 v6, v2
	v_mov_b32_e32 v7, v2
	v_mov_b32_e32 v16, v2
	v_mov_b32_e32 v17, v2
	v_mov_b32_e32 v14, v2
	v_mov_b32_e32 v15, v2
.LBB0_1708:
	v_add_u32_e32 v66, 0x1800, v100
	v_lshl_add_u64 v[34:35], s[20:21], 0, v[66:67]
	v_add_u32_e32 v66, 0x1000, v100
	v_lshl_add_u64 v[36:37], s[20:21], 0, v[66:67]
	v_add_u32_e32 v66, 0x800, v100
	global_load_dwordx4 v[58:61], v[34:35], off
	global_load_dwordx4 v[54:57], v[36:37], off
	v_lshl_add_u64 v[34:35], s[20:21], 0, v[66:67]
	v_mov_b32_e32 v101, v67
	v_lshl_add_u64 v[36:37], s[20:21], 0, v[100:101]
	global_load_dwordx4 v[50:53], v[34:35], off
	global_load_dwordx4 v[42:45], v[36:37], off
	global_load_dwordx2 v[118:119], v[98:99], off offset:3072
	global_load_dwordx2 v[120:121], v[98:99], off offset:2048
	global_load_dwordx2 v[122:123], v[98:99], off offset:1024
	global_load_dwordx2 v[124:125], v[98:99], off
	s_add_i32 s5, s6, 2
	s_cmp_lt_u32 s6, 14
	s_cselect_b64 s[0:1], -1, 0
	s_and_b64 vcc, s[0:1], exec
	s_cselect_b32 s0, s4, 60
	s_sub_i32 s1, 63, s0
	v_lshl_add_u32 v66, s1, 11, v68
	v_lshl_add_u64 v[34:35], s[20:21], 0, v[66:67]
	v_lshl_add_u32 v66, s1, 10, v70
	s_sub_i32 s1, 62, s0
	v_lshl_add_u64 v[38:39], s[28:29], 0, v[66:67]
	v_lshl_add_u32 v66, s1, 11, v68
	s_waitcnt vmcnt(0) lgkmcnt(0)
	v_cvt_pk_f32_fp8_e32 v[162:163], v102
	v_cvt_pk_f32_fp8_sdwa v[146:147], v102 src0_sel:WORD_1
	v_cvt_pk_f32_fp8_e32 v[130:131], v103
	v_cvt_pk_f32_fp8_sdwa v[114:115], v103 src0_sel:WORD_1
	global_load_dwordx2 v[102:103], v[38:39], off
	v_lshl_add_u64 v[38:39], s[20:21], 0, v[66:67]
	v_lshl_add_u32 v66, s1, 10, v70
	s_sub_i32 s1, 61, s0
	v_lshl_add_u64 v[46:47], s[28:29], 0, v[66:67]
	v_lshl_add_u32 v66, s1, 11, v68
	v_cvt_pk_f32_fp8_e32 v[164:165], v104
	v_cvt_pk_f32_fp8_sdwa v[148:149], v104 src0_sel:WORD_1
	v_cvt_pk_f32_fp8_e32 v[132:133], v105
	v_cvt_pk_f32_fp8_sdwa v[116:117], v105 src0_sel:WORD_1
	global_load_dwordx2 v[104:105], v[46:47], off
	v_lshl_add_u64 v[46:47], s[20:21], 0, v[66:67]
	v_lshl_add_u32 v66, s1, 10, v70
	s_sub_i32 s0, 60, s0
	v_lshl_add_u64 v[62:63], s[28:29], 0, v[66:67]
	v_lshl_add_u32 v66, s0, 11, v68
	v_cvt_pk_f32_fp8_e32 v[158:159], v106
	v_cvt_pk_f32_fp8_sdwa v[142:143], v106 src0_sel:WORD_1
	v_cvt_pk_f32_fp8_e32 v[126:127], v107
	v_cvt_pk_f32_fp8_sdwa v[110:111], v107 src0_sel:WORD_1
	global_load_dwordx2 v[106:107], v[62:63], off
	v_lshl_add_u64 v[62:63], s[20:21], 0, v[66:67]
	v_lshl_add_u32 v66, s0, 10, v70
	v_cvt_pk_f32_fp8_e32 v[160:161], v108
	v_cvt_pk_f32_fp8_sdwa v[144:145], v108 src0_sel:WORD_1
	v_cvt_pk_f32_fp8_e32 v[128:129], v109
	v_cvt_pk_f32_fp8_sdwa v[112:113], v109 src0_sel:WORD_1
	v_lshl_add_u64 v[108:109], s[28:29], 0, v[66:67]
	global_load_dwordx2 v[108:109], v[108:109], off
	s_nop 0
	global_load_dwordx4 v[34:37], v[34:35], off
	s_nop 0
	global_load_dwordx4 v[38:41], v[38:39], off
	s_nop 0
	global_load_dwordx4 v[46:49], v[46:47], off
	s_nop 0
	global_load_dwordx4 v[62:65], v[62:63], off
	v_lshlrev_b32_e32 v184, 16, v30
	v_and_b32_e32 v185, 0xffff0000, v30
	v_mul_f32_e32 v30, 0x3fb8aa3b, v184
	v_exp_f32_e32 v186, v30
	v_mul_f32_e32 v30, 0x3fb8aa3b, v185
	v_pk_add_f32 v[2:3], v[2:3], v[184:185]
	v_lshlrev_b32_e32 v184, 16, v26
	v_exp_f32_e32 v187, v30
	v_and_b32_e32 v185, 0xffff0000, v26
	v_mul_f32_e32 v26, 0x3fb8aa3b, v184
	v_exp_f32_e32 v188, v26
	v_mul_f32_e32 v26, 0x3fb8aa3b, v185
	v_exp_f32_e32 v189, v26
	v_pk_add_f32 v[2:3], v[2:3], v[184:185]
	v_lshlrev_b32_e32 v184, 16, v22
	v_and_b32_e32 v185, 0xffff0000, v22
	v_pk_fma_f32 v[14:15], v[14:15], v[186:187], v[162:163]
	v_lshlrev_b32_e32 v162, 16, v18
	v_pk_add_f32 v[2:3], v[2:3], v[184:185]
	v_and_b32_e32 v163, 0xffff0000, v18
	v_mul_f32_e32 v18, 0x3fb8aa3b, v162
	v_pk_fma_f32 v[14:15], v[188:189], v[14:15], v[164:165]
	v_exp_f32_e32 v164, v18
	v_mul_f32_e32 v18, 0x3fb8aa3b, v163
	v_pk_add_f32 v[2:3], v[2:3], v[162:163]
	v_lshlrev_b32_e32 v162, 16, v58
	v_exp_f32_e32 v165, v18
	v_and_b32_e32 v163, 0xffff0000, v58
	v_mul_f32_e32 v18, 0x3fb8aa3b, v162
	v_mul_f32_e32 v22, 0x3fb8aa3b, v184
	v_exp_f32_e32 v184, v18
	v_mul_f32_e32 v18, 0x3fb8aa3b, v163
	v_pk_add_f32 v[2:3], v[2:3], v[162:163]
	v_lshlrev_b32_e32 v162, 16, v54
	v_exp_f32_e32 v190, v22
	v_mul_f32_e32 v22, 0x3fb8aa3b, v185
	v_exp_f32_e32 v185, v18
	v_and_b32_e32 v163, 0xffff0000, v54
	v_mul_f32_e32 v18, 0x3fb8aa3b, v162
	v_exp_f32_e32 v186, v18
	v_mul_f32_e32 v18, 0x3fb8aa3b, v163
	v_pk_add_f32 v[2:3], v[2:3], v[162:163]
	v_lshlrev_b32_e32 v162, 16, v50
	v_exp_f32_e32 v187, v18
	v_and_b32_e32 v163, 0xffff0000, v50
	v_mul_f32_e32 v18, 0x3fb8aa3b, v162
	v_exp_f32_e32 v191, v22
	v_exp_f32_e32 v188, v18
	v_mul_f32_e32 v18, 0x3fb8aa3b, v163
	v_pk_add_f32 v[2:3], v[2:3], v[162:163]
	v_lshlrev_b32_e32 v162, 16, v42
	v_exp_f32_e32 v189, v18
	v_and_b32_e32 v163, 0xffff0000, v42
	v_mul_f32_e32 v18, 0x3fb8aa3b, v162
	v_exp_f32_e32 v192, v18
	v_mul_f32_e32 v18, 0x3fb8aa3b, v163
	v_lshlrev_b32_e32 v30, 16, v31
	v_exp_f32_e32 v193, v18
	v_and_b32_e32 v31, 0xffff0000, v31
	v_mul_f32_e32 v18, 0x3fb8aa3b, v30
	v_pk_fma_f32 v[14:15], v[190:191], v[14:15], v[158:159]
	v_exp_f32_e32 v158, v18
	v_mul_f32_e32 v18, 0x3fb8aa3b, v31
	v_lshlrev_b32_e32 v26, 16, v27
	v_exp_f32_e32 v159, v18
	v_and_b32_e32 v27, 0xffff0000, v27
	v_mul_f32_e32 v18, 0x3fb8aa3b, v26
	v_pk_add_f32 v[4:5], v[4:5], v[30:31]
	v_exp_f32_e32 v30, v18
	v_mul_f32_e32 v18, 0x3fb8aa3b, v27
	v_lshlrev_b32_e32 v22, 16, v23
	v_exp_f32_e32 v31, v18
	v_and_b32_e32 v23, 0xffff0000, v23
	v_mul_f32_e32 v18, 0x3fb8aa3b, v22
	v_pk_add_f32 v[4:5], v[4:5], v[26:27]
	v_exp_f32_e32 v26, v18
	v_mul_f32_e32 v18, 0x3fb8aa3b, v23
	v_exp_f32_e32 v27, v18
	v_pk_add_f32 v[4:5], v[4:5], v[22:23]
	v_lshlrev_b32_e32 v18, 16, v19
	v_and_b32_e32 v19, 0xffff0000, v19
	v_pk_fma_f32 v[16:17], v[16:17], v[158:159], v[146:147]
	v_mul_f32_e32 v22, 0x3fb8aa3b, v18
	v_mul_f32_e32 v23, 0x3fb8aa3b, v19
	v_pk_add_f32 v[4:5], v[4:5], v[18:19]
	v_lshlrev_b32_e32 v18, 16, v59
	v_and_b32_e32 v19, 0xffff0000, v59
	v_pk_fma_f32 v[16:17], v[30:31], v[16:17], v[148:149]
	v_mul_f32_e32 v30, 0x3fb8aa3b, v18
	v_pk_add_f32 v[4:5], v[4:5], v[18:19]
	v_lshlrev_b32_e32 v18, 16, v55
	v_mul_f32_e32 v31, 0x3fb8aa3b, v19
	v_and_b32_e32 v19, 0xffff0000, v55
	v_mul_f32_e32 v42, 0x3fb8aa3b, v18
	v_exp_f32_e32 v22, v22
	v_exp_f32_e32 v23, v23
	v_exp_f32_e32 v54, v42
	v_mul_f32_e32 v42, 0x3fb8aa3b, v19
	v_pk_add_f32 v[4:5], v[4:5], v[18:19]
	v_lshlrev_b32_e32 v18, 16, v51
	v_exp_f32_e32 v55, v42
	v_and_b32_e32 v19, 0xffff0000, v51
	v_mul_f32_e32 v42, 0x3fb8aa3b, v18
	v_exp_f32_e32 v50, v42
	v_mul_f32_e32 v42, 0x3fb8aa3b, v19
	v_pk_add_f32 v[4:5], v[4:5], v[18:19]
	v_lshlrev_b32_e32 v18, 16, v43
	v_and_b32_e32 v19, 0xffff0000, v43
	v_exp_f32_e32 v51, v42
	v_mul_f32_e32 v42, 0x3fb8aa3b, v18
	v_mul_f32_e32 v43, 0x3fb8aa3b, v19
	v_pk_fma_f32 v[16:17], v[26:27], v[16:17], v[142:143]
	v_pk_add_f32 v[4:5], v[4:5], v[18:19]
	v_lshlrev_b32_e32 v18, 16, v32
	v_and_b32_e32 v19, 0xffff0000, v32
	v_cvt_pk_f32_fp8_sdwa v[150:151], v118 src0_sel:WORD_1
	v_exp_f32_e32 v30, v30
	v_exp_f32_e32 v31, v31
	v_pk_fma_f32 v[16:17], v[22:23], v[16:17], v[144:145]
	v_mul_f32_e32 v22, 0x3fb8aa3b, v18
	v_mul_f32_e32 v23, 0x3fb8aa3b, v19
	v_exp_f32_e32 v22, v22
	v_exp_f32_e32 v23, v23
	v_pk_add_f32 v[10:11], v[10:11], v[18:19]
	v_lshlrev_b32_e32 v18, 16, v28
	v_and_b32_e32 v19, 0xffff0000, v28
	v_mul_f32_e32 v26, 0x3fb8aa3b, v18
	v_mul_f32_e32 v27, 0x3fb8aa3b, v19
	v_pk_add_f32 v[10:11], v[10:11], v[18:19]
	v_lshlrev_b32_e32 v18, 16, v24
	v_and_b32_e32 v19, 0xffff0000, v24
	v_cvt_pk_f32_fp8_sdwa v[152:153], v120 src0_sel:WORD_1
	v_exp_f32_e32 v26, v26
	v_exp_f32_e32 v27, v27
	v_mul_f32_e32 v24, 0x3fb8aa3b, v18
	v_pk_add_f32 v[10:11], v[10:11], v[18:19]
	v_lshlrev_b32_e32 v18, 16, v20
	v_cvt_pk_f32_fp8_sdwa v[154:155], v122 src0_sel:WORD_1
	v_pk_fma_f32 v[16:17], v[30:31], v[16:17], v[150:151]
	v_exp_f32_e32 v30, v24
	v_mul_f32_e32 v24, 0x3fb8aa3b, v19
	v_and_b32_e32 v19, 0xffff0000, v20
	v_mul_f32_e32 v20, 0x3fb8aa3b, v18
	v_cvt_pk_f32_fp8_sdwa v[156:157], v124 src0_sel:WORD_1
	v_exp_f32_e32 v42, v42
	v_exp_f32_e32 v43, v43
	v_pk_fma_f32 v[6:7], v[6:7], v[22:23], v[130:131]
	v_exp_f32_e32 v22, v20
	v_mul_f32_e32 v20, 0x3fb8aa3b, v19
	v_pk_add_f32 v[10:11], v[10:11], v[18:19]
	v_lshlrev_b32_e32 v18, 16, v60
	v_exp_f32_e32 v23, v20
	v_and_b32_e32 v19, 0xffff0000, v60
	v_mul_f32_e32 v20, 0x3fb8aa3b, v18
	v_pk_fma_f32 v[16:17], v[54:55], v[16:17], v[152:153]
	v_pk_fma_f32 v[6:7], v[26:27], v[6:7], v[132:133]
	v_exp_f32_e32 v26, v20
	v_mul_f32_e32 v20, 0x3fb8aa3b, v19
	v_pk_add_f32 v[10:11], v[10:11], v[18:19]
	v_lshlrev_b32_e32 v18, 16, v56
	v_pk_fma_f32 v[16:17], v[50:51], v[16:17], v[154:155]
	v_exp_f32_e32 v27, v20
	v_and_b32_e32 v19, 0xffff0000, v56
	v_mul_f32_e32 v20, 0x3fb8aa3b, v18
	v_pk_fma_f32 v[16:17], v[42:43], v[16:17], v[156:157]
	v_exp_f32_e32 v42, v20
	v_mul_f32_e32 v20, 0x3fb8aa3b, v19
	v_pk_add_f32 v[10:11], v[10:11], v[18:19]
	v_lshlrev_b32_e32 v18, 16, v52
	v_exp_f32_e32 v31, v24
	v_exp_f32_e32 v43, v20
	v_and_b32_e32 v19, 0xffff0000, v52
	v_mul_f32_e32 v20, 0x3fb8aa3b, v18
	v_exp_f32_e32 v50, v20
	v_mul_f32_e32 v20, 0x3fb8aa3b, v19
	v_pk_add_f32 v[10:11], v[10:11], v[18:19]
	v_lshlrev_b32_e32 v18, 16, v44
	v_exp_f32_e32 v51, v20
	v_and_b32_e32 v19, 0xffff0000, v44
	v_mul_f32_e32 v20, 0x3fb8aa3b, v18
	v_cvt_pk_f32_fp8_e32 v[134:135], v119
	v_exp_f32_e32 v54, v20
	v_mul_f32_e32 v20, 0x3fb8aa3b, v19
	v_pk_add_f32 v[10:11], v[10:11], v[18:19]
	v_lshlrev_b32_e32 v18, 16, v33
	v_exp_f32_e32 v55, v20
	v_pk_fma_f32 v[6:7], v[30:31], v[6:7], v[126:127]
	v_and_b32_e32 v19, 0xffff0000, v33
	v_mul_f32_e32 v20, 0x3fb8aa3b, v18
	v_pk_fma_f32 v[6:7], v[22:23], v[6:7], v[128:129]
	v_exp_f32_e32 v22, v20
	v_mul_f32_e32 v20, 0x3fb8aa3b, v19
	v_pk_add_f32 v[12:13], v[12:13], v[18:19]
	v_lshlrev_b32_e32 v18, 16, v29
	v_exp_f32_e32 v23, v20
	v_and_b32_e32 v19, 0xffff0000, v29
	v_mul_f32_e32 v20, 0x3fb8aa3b, v18
	v_pk_fma_f32 v[6:7], v[26:27], v[6:7], v[134:135]
	v_exp_f32_e32 v26, v20
	v_mul_f32_e32 v20, 0x3fb8aa3b, v19
	v_pk_add_f32 v[12:13], v[12:13], v[18:19]
	v_lshlrev_b32_e32 v18, 16, v25
	v_exp_f32_e32 v27, v20
	v_and_b32_e32 v19, 0xffff0000, v25
	v_mul_f32_e32 v20, 0x3fb8aa3b, v18
	v_exp_f32_e32 v24, v20
	v_mul_f32_e32 v20, 0x3fb8aa3b, v19
	v_pk_add_f32 v[12:13], v[12:13], v[18:19]
	v_lshlrev_b32_e32 v18, 16, v21
	v_and_b32_e32 v19, 0xffff0000, v21
	v_exp_f32_e32 v25, v20
	v_mul_f32_e32 v20, 0x3fb8aa3b, v18
	v_mul_f32_e32 v21, 0x3fb8aa3b, v19
	v_pk_add_f32 v[12:13], v[12:13], v[18:19]
	v_lshlrev_b32_e32 v18, 16, v61
	v_and_b32_e32 v19, 0xffff0000, v61
	v_pk_fma_f32 v[8:9], v[8:9], v[22:23], v[114:115]
	v_exp_f32_e32 v20, v20
	v_exp_f32_e32 v21, v21
	v_mul_f32_e32 v22, 0x3fb8aa3b, v18
	v_mul_f32_e32 v23, 0x3fb8aa3b, v19
	v_pk_add_f32 v[12:13], v[12:13], v[18:19]
	v_lshlrev_b32_e32 v18, 16, v57
	v_and_b32_e32 v19, 0xffff0000, v57
	v_cvt_pk_f32_fp8_e32 v[176:177], v118
	v_cvt_pk_f32_fp8_sdwa v[118:119], v119 src0_sel:WORD_1
	v_pk_fma_f32 v[8:9], v[26:27], v[8:9], v[116:117]
	v_exp_f32_e32 v22, v22
	v_exp_f32_e32 v23, v23
	v_mul_f32_e32 v26, 0x3fb8aa3b, v18
	v_mul_f32_e32 v27, 0x3fb8aa3b, v19
	v_pk_add_f32 v[12:13], v[12:13], v[18:19]
	v_lshlrev_b32_e32 v18, 16, v53
	v_and_b32_e32 v19, 0xffff0000, v53
	v_cvt_pk_f32_fp8_e32 v[178:179], v120
	v_cvt_pk_f32_fp8_e32 v[136:137], v121
	v_cvt_pk_f32_fp8_sdwa v[120:121], v121 src0_sel:WORD_1
	v_exp_f32_e32 v26, v26
	v_exp_f32_e32 v27, v27
	v_mul_f32_e32 v28, 0x3fb8aa3b, v18
	v_mul_f32_e32 v29, 0x3fb8aa3b, v19
	v_pk_add_f32 v[12:13], v[12:13], v[18:19]
	v_lshlrev_b32_e32 v18, 16, v45
	v_and_b32_e32 v19, 0xffff0000, v45
	v_cvt_pk_f32_fp8_e32 v[180:181], v122
	v_cvt_pk_f32_fp8_e32 v[138:139], v123
	v_cvt_pk_f32_fp8_sdwa v[122:123], v123 src0_sel:WORD_1
	v_exp_f32_e32 v28, v28
	v_exp_f32_e32 v29, v29
	v_mul_f32_e32 v30, 0x3fb8aa3b, v18
	v_mul_f32_e32 v31, 0x3fb8aa3b, v19
	v_pk_fma_f32 v[8:9], v[24:25], v[8:9], v[110:111]
	v_cvt_pk_f32_fp8_e32 v[182:183], v124
	v_cvt_pk_f32_fp8_e32 v[140:141], v125
	v_cvt_pk_f32_fp8_sdwa v[124:125], v125 src0_sel:WORD_1
	v_exp_f32_e32 v30, v30
	v_exp_f32_e32 v31, v31
	v_pk_fma_f32 v[8:9], v[20:21], v[8:9], v[112:113]
	v_pk_fma_f32 v[14:15], v[164:165], v[14:15], v[160:161]
	v_pk_fma_f32 v[8:9], v[22:23], v[8:9], v[118:119]
	v_pk_fma_f32 v[14:15], v[184:185], v[14:15], v[176:177]
	v_pk_fma_f32 v[8:9], v[26:27], v[8:9], v[120:121]
	v_pk_fma_f32 v[14:15], v[186:187], v[14:15], v[178:179]
	v_pk_fma_f32 v[6:7], v[42:43], v[6:7], v[136:137]
	v_pk_fma_f32 v[8:9], v[28:29], v[8:9], v[122:123]
	s_movk_i32 s0, 0xe000
	v_pk_fma_f32 v[14:15], v[188:189], v[14:15], v[180:181]
	v_pk_fma_f32 v[6:7], v[50:51], v[6:7], v[138:139]
	v_pk_fma_f32 v[8:9], v[30:31], v[8:9], v[124:125]
	v_pk_add_f32 v[12:13], v[12:13], v[18:19]
	s_mov_b32 s1, -1
	s_waitcnt vmcnt(0) lgkmcnt(0)
	v_mov_b64_e32 v[18:19], v[62:63]
	v_mov_b64_e32 v[22:23], v[46:47]
	v_mov_b64_e32 v[26:27], v[38:39]
	v_mov_b64_e32 v[30:31], v[34:35]
	v_pk_fma_f32 v[14:15], v[192:193], v[14:15], v[182:183]
	v_pk_add_f32 v[2:3], v[2:3], v[162:163]
	v_pk_fma_f32 v[6:7], v[54:55], v[6:7], v[140:141]
	s_add_i32 s4, s4, 8
	v_lshl_add_u64 v[98:99], v[98:99], 0, s[0:1]
	v_add_u32_e32 v100, 0xffffc000, v100
	s_mov_b32 s6, s5
	v_mov_b64_e32 v[20:21], v[64:65]
	v_mov_b64_e32 v[24:25], v[48:49]
	v_mov_b64_e32 v[28:29], v[40:41]
	v_mov_b64_e32 v[32:33], v[36:37]
	s_cbranch_vccnz .LBB0_1708
	v_mov_b32_e32 v35, 0
	v_mov_b32_e32 v34, v35
	v_mov_b32_e32 v37, v35
	v_mov_b32_e32 v36, v35
	v_mov_b32_e32 v39, v35
	v_mov_b32_e32 v38, v35
	v_mov_b32_e32 v41, v35
	v_mov_b32_e32 v40, v35
	ds_write_b128 v170, v[2:5] offset:32768
	ds_write_b128 v170, v[10:13] offset:32784
	ds_write_b128 v170, v[14:17] offset:49152
	ds_write_b128 v170, v[6:9] offset:49168
	s_waitcnt lgkmcnt(0)
	s_barrier
	s_and_saveexec_b64 s[44:45], s[34:35]
	s_cbranch_execz .LBB0_1719
	v_mov_b32_e32 v66, v67
	v_mov_b32_e32 v2, 0
	v_mov_b64_e32 v[34:35], v[66:67]
	v_mov_b64_e32 v[36:37], v[66:67]
	v_mov_b64_e32 v[38:39], v[66:67]
	v_mov_b64_e32 v[40:41], v[66:67]
	s_and_saveexec_b64 s[46:47], s[14:15]
	s_cbranch_execz .LBB0_1714
	v_mov_b32_e32 v40, 0
	s_mov_b32 s4, 0
	v_mov_b32_e32 v2, v171
	v_mov_b32_e32 v41, v40
	v_mov_b32_e32 v38, v40
	v_mov_b32_e32 v39, v40
	v_mov_b32_e32 v36, v40
	v_mov_b32_e32 v37, v40
	v_mov_b32_e32 v34, v40
	v_mov_b32_e32 v35, v40

.LBB0_1723:
	s_or_b64 exec, exec, s[44:45]
	global_load_dwordx4 v[22:25], v[78:79], off
	s_nop 0
	global_load_dwordx2 v[78:79], v[76:77], off
	global_load_dwordx4 v[18:21], v[80:81], off
	global_load_dwordx4 v[14:17], v[82:83], off
	global_load_dwordx4 v[10:13], v[84:85], off
	global_load_dwordx2 v[64:65], v[76:77], off offset:1024
	global_load_dwordx2 v[62:63], v[76:77], off offset:2048
	global_load_dwordx2 v[60:61], v[76:77], off offset:3072
	s_mov_b32 s5, 0
	v_mov_b32_e32 v42, v69
.LBB0_1724:
	v_add_u32_e32 v66, 0x2000, v42
	v_add_u32_e32 v76, 0x2800, v42
	v_mov_b32_e32 v77, v67
	v_lshl_add_u64 v[2:3], s[18:19], 0, v[66:67]
	v_lshl_add_u64 v[4:5], s[18:19], 0, v[76:77]
	v_add_u32_e32 v54, 0x3000, v42
	v_mov_b32_e32 v55, v67
	v_add_u32_e32 v44, 0x3800, v42
	v_mov_b32_e32 v45, v67
	global_load_dwordx4 v[30:33], v[2:3], off
	global_load_dwordx4 v[26:29], v[4:5], off
	v_lshl_add_u64 v[2:3], s[18:19], 0, v[54:55]
	v_lshl_add_u64 v[4:5], s[18:19], 0, v[44:45]
	global_load_dwordx4 v[6:9], v[2:3], off
	s_nop 0
	global_load_dwordx4 v[2:5], v[4:5], off
	s_nop 0
	global_load_dwordx2 v[82:83], v[74:75], off
	global_load_dwordx2 v[80:81], v[74:75], off offset:1024
	global_load_dwordx2 v[58:59], v[74:75], off offset:2048
	global_load_dwordx2 v[56:57], v[74:75], off offset:3072
	s_waitcnt vmcnt(0) lgkmcnt(0)
	v_lshlrev_b32_e32 v43, 16, v22
	v_and_b32_e32 v22, 0xffff0000, v22
	v_mul_f32_e32 v43, 0x3fb8aa3b, v43
	v_mul_f32_e32 v22, 0x3fb8aa3b, v22
	v_cvt_pk_f32_fp8_e32 v[84:85], v78
	v_exp_f32_e32 v102, v43
	v_exp_f32_e32 v103, v22
	v_lshlrev_b32_e32 v22, 16, v23
	v_and_b32_e32 v23, 0xffff0000, v23
	v_mul_f32_e32 v22, 0x3fb8aa3b, v22
	v_exp_f32_e32 v104, v22
	v_mul_f32_e32 v22, 0x3fb8aa3b, v23
	v_lshlrev_b32_e32 v23, 16, v24
	v_cvt_pk_f32_fp8_sdwa v[98:99], v78 src0_sel:WORD_1
	v_exp_f32_e32 v105, v22
	v_and_b32_e32 v24, 0xffff0000, v24
	v_mul_f32_e32 v23, 0x3fb8aa3b, v23
	v_pk_fma_f32 v[34:35], v[34:35], v[102:103], v[84:85]
	v_exp_f32_e32 v84, v23
	v_mul_f32_e32 v23, 0x3fb8aa3b, v24
	v_exp_f32_e32 v85, v23
	v_lshlrev_b32_e32 v23, 16, v25
	v_and_b32_e32 v24, 0xffff0000, v25
	v_mul_f32_e32 v23, 0x3fb8aa3b, v23
	v_pk_fma_f32 v[36:37], v[36:37], v[104:105], v[98:99]
	v_exp_f32_e32 v98, v23
	v_mul_f32_e32 v23, 0x3fb8aa3b, v24
	v_cvt_pk_f32_fp8_e32 v[100:101], v79
	v_cvt_pk_f32_fp8_sdwa v[78:79], v79 src0_sel:WORD_1
	v_exp_f32_e32 v99, v23
	v_mov_b32_e32 v43, v67
	v_pk_fma_f32 v[38:39], v[38:39], v[84:85], v[100:101]
	v_cvt_pk_bf16_f32 v22, v34, v35
	v_pk_fma_f32 v[40:41], v[40:41], v[98:99], v[78:79]
	v_lshl_add_u64 v[78:79], s[30:31], 0, v[42:43]
	v_lshlrev_b32_e32 v43, 16, v18
	v_and_b32_e32 v18, 0xffff0000, v18
	v_mul_f32_e32 v18, 0x3fb8aa3b, v18
	v_exp_f32_e32 v85, v18
	v_lshlrev_b32_e32 v18, 16, v19
	v_and_b32_e32 v19, 0xffff0000, v19
	v_cvt_pk_bf16_f32 v23, v36, v37
	v_cvt_pk_bf16_f32 v24, v38, v39
	v_cvt_pk_bf16_f32 v25, v40, v41
	v_mul_f32_e32 v18, 0x3fb8aa3b, v18
	v_mul_f32_e32 v19, 0x3fb8aa3b, v19
	global_store_dwordx4 v[78:79], v[22:25], off
	v_exp_f32_e32 v18, v18
	v_exp_f32_e32 v19, v19
	v_cvt_pk_f32_fp8_sdwa v[24:25], v64 src0_sel:WORD_1
	v_mul_f32_e32 v43, 0x3fb8aa3b, v43
	v_cvt_pk_f32_fp8_e32 v[22:23], v64
	v_cvt_pk_f32_fp8_e32 v[78:79], v65
	v_pk_fma_f32 v[24:25], v[18:19], v[36:37], v[24:25]
	v_lshlrev_b32_e32 v18, 16, v20
	v_and_b32_e32 v19, 0xffff0000, v20
	v_lshlrev_b32_e32 v20, 16, v21
	v_and_b32_e32 v21, 0xffff0000, v21
	v_mul_f32_e32 v18, 0x3fb8aa3b, v18
	v_mul_f32_e32 v19, 0x3fb8aa3b, v19
	v_mul_f32_e32 v20, 0x3fb8aa3b, v20
	v_mul_f32_e32 v21, 0x3fb8aa3b, v21
	v_exp_f32_e32 v84, v43
	v_cvt_pk_f32_fp8_sdwa v[98:99], v65 src0_sel:WORD_1
	v_exp_f32_e32 v18, v18
	v_exp_f32_e32 v19, v19
	v_exp_f32_e32 v20, v20
	v_exp_f32_e32 v21, v21
	v_pk_fma_f32 v[64:65], v[84:85], v[34:35], v[22:23]
	v_pk_fma_f32 v[22:23], v[18:19], v[38:39], v[78:79]
	v_cvt_pk_bf16_f32 v34, v64, v65
	v_pk_fma_f32 v[18:19], v[20:21], v[40:41], v[98:99]
	v_add_u32_e32 v20, 0x800, v42
	v_mov_b32_e32 v21, v67
	v_cvt_pk_bf16_f32 v35, v24, v25
	v_cvt_pk_bf16_f32 v36, v22, v23
	v_cvt_pk_bf16_f32 v37, v18, v19
	v_lshl_add_u64 v[20:21], s[30:31], 0, v[20:21]
	global_store_dwordx4 v[20:21], v[34:37], off
	v_lshlrev_b32_e32 v38, 16, v10
	v_and_b32_e32 v10, 0xffff0000, v10
	v_lshlrev_b32_e32 v36, 16, v14
	v_mul_f32_e32 v36, 0x3fb8aa3b, v36
	v_mul_f32_e32 v10, 0x3fb8aa3b, v10
	v_exp_f32_e32 v106, v36
	v_cvt_pk_f32_fp8_e32 v[114:115], v61
	v_cvt_pk_f32_fp8_sdwa v[36:37], v61 src0_sel:WORD_1
	v_exp_f32_e32 v61, v10
	v_lshlrev_b32_e32 v10, 16, v11
	v_and_b32_e32 v11, 0xffff0000, v11
	v_mul_f32_e32 v10, 0x3fb8aa3b, v10
	v_exp_f32_e32 v116, v10
	v_mul_f32_e32 v10, 0x3fb8aa3b, v11
	v_exp_f32_e32 v117, v10
	v_lshlrev_b32_e32 v10, 16, v12
	v_and_b32_e32 v11, 0xffff0000, v12
	v_mul_f32_e32 v10, 0x3fb8aa3b, v10
	v_exp_f32_e32 v118, v10
	v_mul_f32_e32 v10, 0x3fb8aa3b, v11
	v_exp_f32_e32 v119, v10
	v_lshlrev_b32_e32 v10, 16, v13
	v_and_b32_e32 v11, 0xffff0000, v13
	v_mul_f32_e32 v10, 0x3fb8aa3b, v10
	s_add_i32 s4, s5, 2
	v_exp_f32_e32 v120, v10
	v_mul_f32_e32 v10, 0x3fb8aa3b, v11
	s_cmp_lt_u32 s5, 14
	v_exp_f32_e32 v121, v10
	v_add_u32_e32 v10, 0x1800, v42
	v_mov_b32_e32 v11, v67
	s_cselect_b32 s0, s4, 15
	v_lshl_add_u64 v[122:123], s[30:31], 0, v[10:11]
	s_lshl_b32 s1, s0, 2
	v_lshl_add_u32 v10, s0, 13, v68
	s_or_b32 s6, s1, 1
	v_lshl_add_u64 v[124:125], s[18:19], 0, v[10:11]
	v_lshl_add_u32 v10, s0, 12, v70
	v_lshl_add_u64 v[126:127], s[24:25], 0, v[10:11]
	v_lshl_add_u32 v10, s6, 11, v68
	s_or_b32 s7, s1, 2
	v_lshl_add_u64 v[128:129], s[18:19], 0, v[10:11]
	v_lshl_add_u32 v10, s6, 10, v70
	v_lshl_add_u64 v[130:131], s[24:25], 0, v[10:11]
	v_lshl_add_u32 v10, s7, 11, v68
	s_or_b32 s1, s1, 3
	v_lshl_add_u64 v[132:133], s[18:19], 0, v[10:11]
	v_lshl_add_u32 v10, s7, 10, v70
	v_lshl_add_u64 v[134:135], s[24:25], 0, v[10:11]
	v_lshl_add_u32 v10, s1, 11, v68
	v_lshl_add_u64 v[136:137], s[18:19], 0, v[10:11]
	v_lshl_add_u32 v10, s1, 10, v70
	v_lshl_add_u64 v[138:139], s[24:25], 0, v[10:11]
	v_lshlrev_b32_e32 v10, 16, v30
	v_and_b32_e32 v11, 0xffff0000, v30
	v_mul_f32_e32 v10, 0x3fb8aa3b, v10
	v_exp_f32_e32 v140, v10
	v_mul_f32_e32 v10, 0x3fb8aa3b, v11
	v_exp_f32_e32 v141, v10
	v_lshlrev_b32_e32 v10, 16, v31
	v_and_b32_e32 v11, 0xffff0000, v31
	v_mul_f32_e32 v10, 0x3fb8aa3b, v10
	v_exp_f32_e32 v102, v10
	v_mul_f32_e32 v10, 0x3fb8aa3b, v11
	v_exp_f32_e32 v103, v10
	v_lshlrev_b32_e32 v10, 16, v32
	v_and_b32_e32 v11, 0xffff0000, v32
	v_mul_f32_e32 v10, 0x3fb8aa3b, v10
	v_exp_f32_e32 v98, v10
	v_mul_f32_e32 v10, 0x3fb8aa3b, v11
	v_exp_f32_e32 v99, v10
	v_lshlrev_b32_e32 v10, 16, v33
	v_and_b32_e32 v14, 0xffff0000, v14
	v_and_b32_e32 v11, 0xffff0000, v33
	v_mul_f32_e32 v10, 0x3fb8aa3b, v10
	v_mul_f32_e32 v14, 0x3fb8aa3b, v14
	v_mul_f32_e32 v38, 0x3fb8aa3b, v38
	v_cvt_pk_f32_fp8_e32 v[100:101], v82
	v_cvt_pk_f32_fp8_sdwa v[84:85], v82 src0_sel:WORD_1
	v_exp_f32_e32 v82, v10
	v_mul_f32_e32 v10, 0x3fb8aa3b, v11
	v_exp_f32_e32 v107, v14
	v_lshlrev_b32_e32 v14, 16, v15
	v_cvt_pk_f32_fp8_e32 v[110:111], v60
	v_cvt_pk_f32_fp8_sdwa v[112:113], v60 src0_sel:WORD_1
	v_exp_f32_e32 v60, v38
	v_cvt_pk_f32_fp8_e32 v[38:39], v83
	v_cvt_pk_f32_fp8_sdwa v[40:41], v83 src0_sel:WORD_1
	v_exp_f32_e32 v83, v10
	v_lshlrev_b32_e32 v10, 16, v26
	v_and_b32_e32 v15, 0xffff0000, v15
	v_mul_f32_e32 v14, 0x3fb8aa3b, v14
	v_and_b32_e32 v11, 0xffff0000, v26
	v_mul_f32_e32 v10, 0x3fb8aa3b, v10
	v_exp_f32_e32 v108, v14
	v_mul_f32_e32 v14, 0x3fb8aa3b, v15
	v_cvt_pk_f32_fp8_e32 v[142:143], v80
	v_cvt_pk_f32_fp8_sdwa v[144:145], v80 src0_sel:WORD_1
	v_exp_f32_e32 v80, v10
	v_mul_f32_e32 v10, 0x3fb8aa3b, v11
	v_exp_f32_e32 v109, v14
	v_lshlrev_b32_e32 v14, 16, v16
	v_cvt_pk_f32_fp8_e32 v[146:147], v81
	v_cvt_pk_f32_fp8_sdwa v[32:33], v81 src0_sel:WORD_1
	v_exp_f32_e32 v81, v10
	v_lshlrev_b32_e32 v10, 16, v27
	v_and_b32_e32 v15, 0xffff0000, v16
	v_mul_f32_e32 v14, 0x3fb8aa3b, v14
	v_and_b32_e32 v11, 0xffff0000, v27
	v_mul_f32_e32 v10, 0x3fb8aa3b, v10
	v_cvt_pk_f32_fp8_e32 v[78:79], v62
	v_cvt_pk_f32_fp8_sdwa v[104:105], v62 src0_sel:WORD_1
	v_exp_f32_e32 v62, v14
	v_mul_f32_e32 v14, 0x3fb8aa3b, v15
	v_exp_f32_e32 v148, v10
	v_mul_f32_e32 v10, 0x3fb8aa3b, v11
	v_cvt_pk_f32_fp8_e32 v[34:35], v63
	v_cvt_pk_f32_fp8_sdwa v[20:21], v63 src0_sel:WORD_1
	v_exp_f32_e32 v63, v14
	v_lshlrev_b32_e32 v14, 16, v17
	v_and_b32_e32 v15, 0xffff0000, v17
	v_exp_f32_e32 v149, v10
	v_lshlrev_b32_e32 v10, 16, v28
	v_mul_f32_e32 v14, 0x3fb8aa3b, v14
	v_mul_f32_e32 v15, 0x3fb8aa3b, v15
	v_and_b32_e32 v11, 0xffff0000, v28
	v_mul_f32_e32 v10, 0x3fb8aa3b, v10
	v_exp_f32_e32 v14, v14
	v_exp_f32_e32 v15, v15
	v_exp_f32_e32 v150, v10
	v_mul_f32_e32 v10, 0x3fb8aa3b, v11
	v_exp_f32_e32 v151, v10
	v_lshlrev_b32_e32 v10, 16, v29
	v_and_b32_e32 v11, 0xffff0000, v29
	v_mul_f32_e32 v10, 0x3fb8aa3b, v10
	v_exp_f32_e32 v28, v10
	v_mul_f32_e32 v10, 0x3fb8aa3b, v11
	v_pk_fma_f32 v[12:13], v[106:107], v[64:65], v[78:79]
	v_exp_f32_e32 v29, v10
	v_cvt_pk_bf16_f32 v10, v12, v13
	v_pk_fma_f32 v[106:107], v[60:61], v[12:13], v[110:111]
	v_pk_fma_f32 v[12:13], v[108:109], v[24:25], v[104:105]
	v_pk_fma_f32 v[22:23], v[62:63], v[22:23], v[34:35]
	v_pk_fma_f32 v[14:15], v[14:15], v[18:19], v[20:21]
	v_add_u32_e32 v16, 0x1000, v42
	v_mov_b32_e32 v17, v67
	v_pk_fma_f32 v[104:105], v[116:117], v[12:13], v[112:113]
	v_pk_fma_f32 v[108:109], v[118:119], v[22:23], v[114:115]
	v_pk_fma_f32 v[110:111], v[120:121], v[14:15], v[36:37]
	v_lshl_add_u64 v[16:17], s[30:31], 0, v[16:17]
	v_cvt_pk_bf16_f32 v60, v106, v107
	v_cvt_pk_bf16_f32 v11, v12, v13
	v_cvt_pk_bf16_f32 v61, v104, v105
	v_cvt_pk_bf16_f32 v12, v22, v23
	v_cvt_pk_bf16_f32 v62, v108, v109
	v_cvt_pk_bf16_f32 v13, v14, v15
	v_cvt_pk_bf16_f32 v63, v110, v111
	global_store_dwordx4 v[16:17], v[10:13], off
	global_store_dwordx4 v[122:123], v[60:63], off
	global_load_dwordx4 v[22:25], v[124:125], off
	global_load_dwordx2 v[78:79], v[126:127], off
	global_load_dwordx4 v[18:21], v[128:129], off
	global_load_dwordx2 v[64:65], v[130:131], off
	global_load_dwordx4 v[14:17], v[132:133], off
	global_load_dwordx2 v[62:63], v[134:135], off
	global_load_dwordx4 v[10:13], v[136:137], off
	global_load_dwordx2 v[60:61], v[138:139], off
	v_lshlrev_b32_e32 v34, 16, v6
	v_and_b32_e32 v6, 0xffff0000, v6
	v_mul_f32_e32 v6, 0x3fb8aa3b, v6
	v_exp_f32_e32 v35, v6
	v_lshlrev_b32_e32 v6, 16, v7
	v_and_b32_e32 v7, 0xffff0000, v7
	v_mul_f32_e32 v6, 0x3fb8aa3b, v6
	v_exp_f32_e32 v36, v6
	v_mul_f32_e32 v6, 0x3fb8aa3b, v7
	v_exp_f32_e32 v37, v6
	v_lshlrev_b32_e32 v6, 16, v8
	v_and_b32_e32 v7, 0xffff0000, v8
	v_mul_f32_e32 v6, 0x3fb8aa3b, v6
	v_exp_f32_e32 v114, v6
	v_mul_f32_e32 v6, 0x3fb8aa3b, v7
	v_exp_f32_e32 v115, v6
	v_lshlrev_b32_e32 v6, 16, v9
	v_and_b32_e32 v7, 0xffff0000, v9
	v_mul_f32_e32 v6, 0x3fb8aa3b, v6
	v_exp_f32_e32 v116, v6
	v_mul_f32_e32 v6, 0x3fb8aa3b, v7
	v_mul_f32_e32 v34, 0x3fb8aa3b, v34
	v_exp_f32_e32 v117, v6
	v_lshlrev_b32_e32 v6, 16, v2
	v_and_b32_e32 v2, 0xffff0000, v2
	v_lshl_add_u64 v[26:27], s[30:31], 0, v[76:77]
	v_cvt_pk_f32_fp8_e32 v[76:77], v58
	v_exp_f32_e32 v34, v34
	v_mul_f32_e32 v6, 0x3fb8aa3b, v6
	v_mul_f32_e32 v2, 0x3fb8aa3b, v2
	v_cvt_pk_f32_fp8_e32 v[8:9], v56
	v_cvt_pk_f32_fp8_sdwa v[120:121], v56 src0_sel:WORD_1
	v_cvt_pk_f32_fp8_e32 v[122:123], v57
	v_cvt_pk_f32_fp8_sdwa v[124:125], v57 src0_sel:WORD_1
	v_exp_f32_e32 v56, v6
	v_exp_f32_e32 v57, v2
	v_pk_fma_f32 v[6:7], v[140:141], v[106:107], v[100:101]
	v_lshl_add_u64 v[118:119], s[30:31], 0, v[54:55]
	v_cvt_pk_bf16_f32 v2, v6, v7
	v_pk_fma_f32 v[54:55], v[80:81], v[6:7], v[142:143]
	v_lshlrev_b32_e32 v7, 16, v3
	v_and_b32_e32 v3, 0xffff0000, v3
	v_cvt_pk_f32_fp8_sdwa v[152:153], v58 src0_sel:WORD_1
	v_pk_fma_f32 v[34:35], v[34:35], v[54:55], v[76:77]
	v_mul_f32_e32 v7, 0x3fb8aa3b, v7
	v_mul_f32_e32 v3, 0x3fb8aa3b, v3
	v_cvt_pk_bf16_f32 v6, v54, v55
	v_cvt_pk_bf16_f32 v54, v34, v35
	v_pk_fma_f32 v[34:35], v[56:57], v[34:35], v[8:9]
	v_exp_f32_e32 v8, v7
	v_exp_f32_e32 v9, v3
	v_pk_fma_f32 v[56:57], v[102:103], v[104:105], v[84:85]
	v_cvt_pk_f32_fp8_e32 v[112:113], v59
	v_cvt_pk_bf16_f32 v3, v56, v57
	v_pk_fma_f32 v[56:57], v[148:149], v[56:57], v[144:145]
	s_cmp_gt_u32 s5, 13
	v_pk_fma_f32 v[36:37], v[36:37], v[56:57], v[152:153]
	v_cvt_pk_bf16_f32 v7, v56, v57
	v_cvt_pk_bf16_f32 v55, v36, v37
	v_pk_fma_f32 v[36:37], v[8:9], v[36:37], v[120:121]
	v_lshlrev_b32_e32 v8, 16, v4
	v_and_b32_e32 v4, 0xffff0000, v4
	v_mul_f32_e32 v8, 0x3fb8aa3b, v8
	v_mul_f32_e32 v4, 0x3fb8aa3b, v4
	v_exp_f32_e32 v76, v8
	v_exp_f32_e32 v77, v4
	v_pk_fma_f32 v[8:9], v[98:99], v[108:109], v[38:39]
	v_lshl_add_u64 v[30:31], s[30:31], 0, v[66:67]
	v_pk_fma_f32 v[38:39], v[150:151], v[8:9], v[146:147]
	v_cvt_pk_bf16_f32 v4, v8, v9
	v_cvt_pk_bf16_f32 v8, v38, v39
	v_pk_fma_f32 v[38:39], v[114:115], v[38:39], v[112:113]
	v_lshlrev_b32_e32 v9, 16, v5
	v_and_b32_e32 v5, 0xffff0000, v5
	v_mul_f32_e32 v9, 0x3fb8aa3b, v9
	v_mul_f32_e32 v5, 0x3fb8aa3b, v5
	v_cvt_pk_bf16_f32 v56, v38, v39
	v_pk_fma_f32 v[38:39], v[76:77], v[38:39], v[122:123]
	v_cvt_pk_f32_fp8_sdwa v[58:59], v59 src0_sel:WORD_1
	v_cvt_pk_bf16_f32 v100, v34, v35
	v_cvt_pk_bf16_f32 v101, v36, v37
	v_exp_f32_e32 v80, v9
	v_exp_f32_e32 v81, v5
	v_cvt_pk_bf16_f32 v102, v38, v39
	v_pk_fma_f32 v[40:41], v[82:83], v[110:111], v[40:41]
	v_add_u32_e32 v42, 0x4000, v42
	v_cvt_pk_bf16_f32 v5, v40, v41
	global_store_dwordx4 v[30:31], v[2:5], off
	v_lshl_add_u64 v[74:75], v[74:75], 0, s[40:41]
	s_mov_b32 s5, s4
	v_pk_fma_f32 v[2:3], v[28:29], v[40:41], v[32:33]
	s_nop 0
	v_cvt_pk_bf16_f32 v9, v2, v3
	v_pk_fma_f32 v[2:3], v[116:117], v[2:3], v[58:59]
	global_store_dwordx4 v[26:27], v[6:9], off
	v_pk_fma_f32 v[40:41], v[80:81], v[2:3], v[124:125]
	v_cvt_pk_bf16_f32 v57, v2, v3
	v_cvt_pk_bf16_f32 v103, v40, v41
	v_lshl_add_u64 v[2:3], s[30:31], 0, v[44:45]
	global_store_dwordx4 v[118:119], v[54:57], off
	global_store_dwordx4 v[2:3], v[100:103], off
	s_cbranch_scc0 .LBB0_1724
	v_lshl_add_u64 v[2:3], s[30:31], 0, v[86:87]
	global_load_dwordx4 v[42:45], v[88:89], off
	s_nop 0
	global_load_dwordx2 v[88:89], v[96:97], off
	v_lshl_add_u64 v[4:5], s[26:27], 0, v[86:87]
	global_load_dwordx4 v[38:41], v[92:93], off
	global_load_dwordx4 v[30:33], v[2:3], off
	global_load_dwordx2 v[74:75], v[94:95], off
	v_lshl_add_u64 v[2:3], s[30:31], 0, v[90:91]
	s_waitcnt vmcnt(0) lgkmcnt(0)
	global_load_dwordx4 v[14:17], v[4:5], off
	global_load_dwordx4 v[6:9], v[2:3], off
	v_lshl_add_u64 v[2:3], s[26:27], 0, v[90:91]
	global_load_dwordx4 v[2:5], v[2:3], off
	v_add_u32_e32 v54, 0x1f800, v69
	v_lshl_add_u64 v[56:57], s[22:23], 0, v[72:73]
	s_mov_b32 s0, 0
	s_mov_b32 s4, 4
.LBB0_1726:
	v_add_u32_e32 v66, 0xfffff000, v54
	v_lshl_add_u64 v[10:11], s[20:21], 0, v[66:67]
	global_load_dwordx4 v[122:125], v[10:11], off
	v_lshl_add_u64 v[10:11], s[30:31], 0, v[66:67]
	v_lshl_add_u64 v[60:61], s[26:27], 0, v[66:67]
	v_add_u32_e32 v66, 0xffffe800, v54
	global_load_dwordx4 v[26:29], v[10:11], off
	global_load_dwordx4 v[22:25], v[60:61], off
	v_lshl_add_u64 v[10:11], s[20:21], 0, v[66:67]
	global_load_dwordx4 v[34:37], v[10:11], off
	global_load_dwordx2 v[62:63], v[56:57], off offset:1024
	global_load_dwordx2 v[126:127], v[56:57], off
	v_lshl_add_u64 v[10:11], s[30:31], 0, v[66:67]
	v_lshl_add_u64 v[58:59], s[26:27], 0, v[66:67]
	global_load_dwordx4 v[18:21], v[10:11], off
	s_nop 0
	global_load_dwordx4 v[10:13], v[58:59], off
	s_waitcnt vmcnt(0) lgkmcnt(0)
	v_lshlrev_b32_e32 v55, 16, v42
	v_and_b32_e32 v42, 0xffff0000, v42
	v_mul_f32_e32 v42, 0x3fb8aa3b, v42
	v_exp_f32_e32 v131, v42
	v_lshlrev_b32_e32 v42, 16, v43
	v_and_b32_e32 v43, 0xffff0000, v43
	v_mul_f32_e32 v42, 0x3fb8aa3b, v42
	v_exp_f32_e32 v120, v42
	v_mul_f32_e32 v42, 0x3fb8aa3b, v43
	v_exp_f32_e32 v121, v42
	v_lshlrev_b32_e32 v42, 16, v44
	v_and_b32_e32 v43, 0xffff0000, v44
	v_mul_f32_e32 v42, 0x3fb8aa3b, v42
	v_exp_f32_e32 v106, v42
	v_mul_f32_e32 v42, 0x3fb8aa3b, v43
	v_exp_f32_e32 v107, v42
	v_lshlrev_b32_e32 v42, 16, v45
	v_mul_f32_e32 v55, 0x3fb8aa3b, v55
	v_and_b32_e32 v43, 0xffff0000, v45
	v_mul_f32_e32 v42, 0x3fb8aa3b, v42
	v_exp_f32_e32 v130, v55
	v_exp_f32_e32 v92, v42
	v_mul_f32_e32 v42, 0x3fb8aa3b, v43
	v_mov_b32_e32 v55, v67
	v_exp_f32_e32 v93, v42
	v_lshl_add_u64 v[42:43], s[26:27], 0, v[54:55]
	v_lshlrev_b32_e32 v55, 16, v38
	v_mul_f32_e32 v55, 0x3fb8aa3b, v55
	v_exp_f32_e32 v134, v55
	s_waitcnt vmcnt(0) lgkmcnt(0)
	v_lshlrev_b32_e32 v55, 16, v122
	v_cvt_pk_f32_fp8_e32 v[136:137], v62
	v_cvt_pk_f32_fp8_sdwa v[110:111], v62 src0_sel:WORD_1
	v_and_b32_e32 v62, 0xffff0000, v122
	v_mul_f32_e32 v55, 0x3fb8aa3b, v55
	v_exp_f32_e32 v138, v55
	v_mul_f32_e32 v55, 0x3fb8aa3b, v62
	v_exp_f32_e32 v139, v55
	v_lshlrev_b32_e32 v55, 16, v123
	v_and_b32_e32 v62, 0xffff0000, v123
	v_mul_f32_e32 v55, 0x3fb8aa3b, v55
	v_cvt_pk_f32_fp8_e32 v[128:129], v88
	s_add_i32 s5, s0, 2
	v_exp_f32_e32 v112, v55
	v_mul_f32_e32 v55, 0x3fb8aa3b, v62
	s_cmp_lt_u32 s0, 30
	v_exp_f32_e32 v113, v55
	v_lshlrev_b32_e32 v55, 16, v124
	s_cselect_b32 s1, s4, 62
	v_and_b32_e32 v62, 0xffff0000, v124
	v_mul_f32_e32 v55, 0x3fb8aa3b, v55
	s_sub_i32 s6, 63, s1
	v_exp_f32_e32 v98, v55
	v_mul_f32_e32 v55, 0x3fb8aa3b, v62
	s_sub_i32 s1, 62, s1
	v_lshl_add_u32 v64, s6, 10, v70
	v_mov_b32_e32 v65, v67
	v_exp_f32_e32 v99, v55
	v_lshlrev_b32_e32 v55, 16, v125
	v_pk_fma_f32 v[50:51], v[50:51], v[130:131], v[128:129]
	v_lshlrev_b32_e32 v128, 16, v14
	v_cvt_pk_f32_fp8_e32 v[132:133], v74
	v_cvt_pk_f32_fp8_sdwa v[114:115], v74 src0_sel:WORD_1
	v_cvt_pk_f32_fp8_e32 v[100:101], v75
	v_cvt_pk_f32_fp8_sdwa v[44:45], v75 src0_sel:WORD_1
	v_lshl_add_u64 v[74:75], s[28:29], 0, v[64:65]
	v_lshl_add_u32 v64, s1, 10, v70
	v_and_b32_e32 v62, 0xffff0000, v125
	v_mul_f32_e32 v55, 0x3fb8aa3b, v55
	v_and_b32_e32 v129, 0xffff0000, v14
	v_mul_f32_e32 v14, 0x3d372713, v128
	v_lshl_add_u64 v[82:83], s[28:29], 0, v[64:65]
	v_cvt_pk_f32_fp8_e32 v[96:97], v63
	v_cvt_pk_f32_fp8_sdwa v[64:65], v63 src0_sel:WORD_1
	v_exp_f32_e32 v72, v55
	v_mul_f32_e32 v55, 0x3fb8aa3b, v62
	v_cvt_pk_f32_fp8_e32 v[122:123], v126
	v_cvt_pk_f32_fp8_sdwa v[108:109], v126 src0_sel:WORD_1
	v_cvt_pk_f32_fp8_e32 v[94:95], v127
	v_cvt_pk_f32_fp8_sdwa v[62:63], v127 src0_sel:WORD_1
	v_lshlrev_b32_e32 v126, 16, v30
	v_and_b32_e32 v127, 0xffff0000, v30
	v_mul_f32_e32 v14, v14, v128
	v_mov_b32_e32 v30, v128
	v_fmac_f32_e32 v30, v14, v30
	v_mul_f32_e32 v14, 0x3f4c422a, v30
	v_add_f32_e32 v14, v14, v14
	v_mul_f32_e32 v14, 0x3fb8aa3b, v14
	v_exp_f32_e32 v14, v14
	v_mov_b32_e32 v30, v129
	v_pk_add_f32 v[126:127], v[50:51], v[126:127]
	v_and_b32_e32 v38, 0xffff0000, v38
	v_add_f32_e32 v14, 1.0, v14
	v_rcp_f32_e32 v130, v14
	v_mul_f32_e32 v14, 0x3d372713, v129
	v_mul_f32_e32 v14, v14, v129
	v_fmac_f32_e32 v30, v14, v30
	v_mul_f32_e32 v14, 0x3f4c422a, v30
	v_add_f32_e32 v14, v14, v14
	v_mul_f32_e32 v14, 0x3fb8aa3b, v14
	v_exp_f32_e32 v14, v14
	v_pk_mul_f32 v[128:129], v[128:129], 0.5 op_sel_hi:[1,0]
	v_pk_mul_f32 v[126:127], v[126:127], s[42:43] op_sel_hi:[1,0]
	v_mul_f32_e32 v38, 0x3fb8aa3b, v38
	v_add_f32_e32 v14, 1.0, v14
	v_rcp_f32_e32 v131, v14
	v_exp_f32_e32 v135, v38
	v_exp_f32_e32 v73, v55
	v_lshlrev_b32_e32 v55, 16, v34
	v_pk_fma_f32 v[130:131], v[130:131], 2.0, 1.0 op_sel_hi:[1,0,0] neg_lo:[1,0,0] neg_hi:[1,0,0]
	v_pk_fma_f32 v[50:51], v[134:135], v[50:51], v[132:133]
	v_pk_add_f32 v[130:131], v[130:131], 1.0 op_sel_hi:[1,0]
	v_and_b32_e32 v34, 0xffff0000, v34
	v_pk_mul_f32 v[128:129], v[128:129], v[130:131]
	v_mul_f32_e32 v55, 0x3fb8aa3b, v55
	v_pk_mul_f32 v[126:127], v[126:127], v[128:129]
	v_lshlrev_b32_e32 v128, 16, v2
	v_and_b32_e32 v129, 0xffff0000, v2
	v_mul_f32_e32 v2, 0x3d372713, v128
	v_cvt_pk_bf16_f32 v14, v126, v127
	v_lshlrev_b32_e32 v126, 16, v6
	v_and_b32_e32 v127, 0xffff0000, v6
	v_mul_f32_e32 v2, v2, v128
	v_mov_b32_e32 v6, v128
	v_fmac_f32_e32 v6, v2, v6
	v_mul_f32_e32 v2, 0x3f4c422a, v6
	v_add_f32_e32 v2, v2, v2
	v_mul_f32_e32 v2, 0x3fb8aa3b, v2
	v_exp_f32_e32 v2, v2
	v_mov_b32_e32 v6, v129
	v_pk_add_f32 v[126:127], v[50:51], v[126:127]
	v_mul_f32_e32 v34, 0x3fb8aa3b, v34
	v_add_f32_e32 v2, 1.0, v2
	v_rcp_f32_e32 v130, v2
	v_mul_f32_e32 v2, 0x3d372713, v129
	v_mul_f32_e32 v2, v2, v129
	v_fmac_f32_e32 v6, v2, v6
	v_mul_f32_e32 v2, 0x3f4c422a, v6
	v_add_f32_e32 v2, v2, v2
	v_mul_f32_e32 v2, 0x3fb8aa3b, v2
	v_exp_f32_e32 v2, v2
	v_pk_mul_f32 v[128:129], v[128:129], 0.5 op_sel_hi:[1,0]
	v_pk_mul_f32 v[126:127], v[126:127], s[42:43] op_sel_hi:[1,0]
	v_exp_f32_e32 v124, v55
	v_add_f32_e32 v2, 1.0, v2
	v_rcp_f32_e32 v131, v2
	v_exp_f32_e32 v125, v34
	v_pk_fma_f32 v[50:51], v[138:139], v[50:51], v[136:137]
	v_cvt_pk_f32_fp8_sdwa v[118:119], v88 src0_sel:WORD_1
	v_pk_fma_f32 v[130:131], v[130:131], 2.0, 1.0 op_sel_hi:[1,0,0] neg_lo:[1,0,0] neg_hi:[1,0,0]
	v_lshlrev_b32_e32 v38, 16, v39
	v_pk_add_f32 v[130:131], v[130:131], 1.0 op_sel_hi:[1,0]
	v_pk_fma_f32 v[48:49], v[48:49], v[120:121], v[118:119]
	v_pk_mul_f32 v[128:129], v[128:129], v[130:131]
	v_lshlrev_b32_e32 v118, 16, v15
	v_pk_mul_f32 v[126:127], v[128:129], v[126:127]
	v_lshlrev_b32_e32 v128, 16, v22
	v_mul_f32_e32 v6, 0x3d372713, v128
	v_and_b32_e32 v129, 0xffff0000, v22
	v_mul_f32_e32 v6, v6, v128
	v_mov_b32_e32 v22, v128
	v_fmac_f32_e32 v22, v6, v22
	v_mul_f32_e32 v6, 0x3f4c422a, v22
	v_add_f32_e32 v6, v6, v6
	v_mul_f32_e32 v6, 0x3fb8aa3b, v6
	v_exp_f32_e32 v6, v6
	v_mov_b32_e32 v22, v129
	v_cvt_pk_bf16_f32 v2, v126, v127
	v_lshlrev_b32_e32 v126, 16, v26
	v_add_f32_e32 v6, 1.0, v6
	v_rcp_f32_e32 v130, v6
	v_mul_f32_e32 v6, 0x3d372713, v129
	v_mul_f32_e32 v6, v6, v129
	v_fmac_f32_e32 v22, v6, v22
	v_mul_f32_e32 v6, 0x3f4c422a, v22
	v_add_f32_e32 v6, v6, v6
	v_mul_f32_e32 v6, 0x3fb8aa3b, v6
	v_exp_f32_e32 v6, v6
	v_and_b32_e32 v127, 0xffff0000, v26
	v_pk_add_f32 v[126:127], v[50:51], v[126:127]
	v_pk_fma_f32 v[50:51], v[124:125], v[50:51], v[122:123]
	v_add_f32_e32 v6, 1.0, v6
	v_lshlrev_b32_e32 v124, 16, v10
	v_rcp_f32_e32 v131, v6
	v_mul_f32_e32 v6, 0x3d372713, v124
	v_and_b32_e32 v125, 0xffff0000, v10
	v_mul_f32_e32 v6, v6, v124
	v_mov_b32_e32 v10, v124
	v_fmac_f32_e32 v10, v6, v10
	v_mul_f32_e32 v6, 0x3f4c422a, v10
	v_add_f32_e32 v6, v6, v6
	v_mul_f32_e32 v6, 0x3fb8aa3b, v6
	v_exp_f32_e32 v6, v6
	v_pk_fma_f32 v[130:131], v[130:131], 2.0, 1.0 op_sel_hi:[1,0,0] neg_lo:[1,0,0] neg_hi:[1,0,0]
	v_pk_mul_f32 v[128:129], v[128:129], 0.5 op_sel_hi:[1,0]
	v_pk_add_f32 v[130:131], v[130:131], 1.0 op_sel_hi:[1,0]
	v_pk_mul_f32 v[126:127], v[126:127], s[42:43] op_sel_hi:[1,0]
	v_pk_mul_f32 v[128:129], v[128:129], v[130:131]
	v_add_f32_e32 v6, 1.0, v6
	v_pk_mul_f32 v[126:127], v[128:129], v[126:127]
	v_mov_b32_e32 v10, v125
	v_cvt_pk_bf16_f32 v22, v126, v127
	v_rcp_f32_e32 v126, v6
	v_mul_f32_e32 v6, 0x3d372713, v125
	v_mul_f32_e32 v6, v6, v125
	v_fmac_f32_e32 v10, v6, v10
	v_mul_f32_e32 v6, 0x3f4c422a, v10
	v_add_f32_e32 v6, v6, v6
	v_mul_f32_e32 v6, 0x3fb8aa3b, v6
	v_exp_f32_e32 v6, v6
	v_lshlrev_b32_e32 v122, 16, v18
	v_and_b32_e32 v123, 0xffff0000, v18
	v_and_b32_e32 v18, 0xffff0000, v35
	v_add_f32_e32 v6, 1.0, v6
	v_rcp_f32_e32 v127, v6
	v_lshlrev_b32_e32 v6, 16, v35
	v_mul_f32_e32 v6, 0x3fb8aa3b, v6
	v_exp_f32_e32 v34, v6
	v_mul_f32_e32 v6, 0x3fb8aa3b, v18
	v_exp_f32_e32 v35, v6
	v_mul_f32_e32 v6, 0x3d372713, v118
	v_and_b32_e32 v119, 0xffff0000, v15
	v_mul_f32_e32 v6, v6, v118
	v_mov_b32_e32 v15, v118
	v_fmac_f32_e32 v15, v6, v15
	v_mul_f32_e32 v6, 0x3f4c422a, v15
	v_add_f32_e32 v6, v6, v6
	v_mul_f32_e32 v6, 0x3fb8aa3b, v6
	v_exp_f32_e32 v6, v6
	v_mov_b32_e32 v15, v119
	v_and_b32_e32 v39, 0xffff0000, v39
	v_mul_f32_e32 v38, 0x3fb8aa3b, v38
	v_add_f32_e32 v6, 1.0, v6
	v_rcp_f32_e32 v120, v6
	v_mul_f32_e32 v6, 0x3d372713, v119
	v_mul_f32_e32 v6, v6, v119
	v_fmac_f32_e32 v15, v6, v15
	v_mul_f32_e32 v6, 0x3f4c422a, v15
	v_add_f32_e32 v6, v6, v6
	v_mul_f32_e32 v6, 0x3fb8aa3b, v6
	v_exp_f32_e32 v6, v6
	v_exp_f32_e32 v116, v38
	v_mul_f32_e32 v38, 0x3fb8aa3b, v39
	v_exp_f32_e32 v117, v38
	v_add_f32_e32 v6, 1.0, v6
	v_rcp_f32_e32 v121, v6
	v_lshlrev_b32_e32 v30, 16, v31
	v_and_b32_e32 v31, 0xffff0000, v31
	v_pk_mul_f32 v[118:119], v[118:119], 0.5 op_sel_hi:[1,0]
	v_pk_fma_f32 v[120:121], v[120:121], 2.0, 1.0 op_sel_hi:[1,0,0] neg_lo:[1,0,0] neg_hi:[1,0,0]
	v_pk_add_f32 v[30:31], v[48:49], v[30:31]
	v_pk_add_f32 v[120:121], v[120:121], 1.0 op_sel_hi:[1,0]
	v_pk_mul_f32 v[30:31], v[30:31], s[42:43] op_sel_hi:[1,0]
	v_pk_mul_f32 v[118:119], v[118:119], v[120:121]
	v_lshlrev_b32_e32 v6, 16, v7
	v_pk_mul_f32 v[30:31], v[118:119], v[30:31]
	v_and_b32_e32 v7, 0xffff0000, v7
	v_cvt_pk_bf16_f32 v15, v30, v31
	v_pk_fma_f32 v[30:31], v[116:117], v[48:49], v[114:115]
	v_lshlrev_b32_e32 v48, 16, v3
	v_and_b32_e32 v49, 0xffff0000, v3
	v_mul_f32_e32 v3, 0x3d372713, v48
	v_mul_f32_e32 v3, v3, v48
	v_mov_b32_e32 v18, v48
	v_fmac_f32_e32 v18, v3, v18
	v_mul_f32_e32 v3, 0x3f4c422a, v18
	v_add_f32_e32 v3, v3, v3
	v_mul_f32_e32 v3, 0x3fb8aa3b, v3
	v_exp_f32_e32 v3, v3
	v_mov_b32_e32 v18, v49
	v_pk_add_f32 v[6:7], v[30:31], v[6:7]
	v_lshlrev_b32_e32 v26, 16, v27
	v_add_f32_e32 v3, 1.0, v3
	v_rcp_f32_e32 v114, v3
	v_mul_f32_e32 v3, 0x3d372713, v49
	v_mul_f32_e32 v3, v3, v49
	v_fmac_f32_e32 v18, v3, v18
	v_mul_f32_e32 v3, 0x3f4c422a, v18
	v_add_f32_e32 v3, v3, v3
	v_mul_f32_e32 v3, 0x3fb8aa3b, v3
	v_exp_f32_e32 v3, v3
	v_pk_mul_f32 v[48:49], v[48:49], 0.5 op_sel_hi:[1,0]
	v_pk_mul_f32 v[6:7], v[6:7], s[42:43] op_sel_hi:[1,0]
	v_and_b32_e32 v27, 0xffff0000, v27
	v_add_f32_e32 v3, 1.0, v3
	v_rcp_f32_e32 v115, v3
	v_cvt_pk_f32_fp8_e32 v[104:105], v89
	v_lshlrev_b32_e32 v38, 16, v40
	v_and_b32_e32 v39, 0xffff0000, v40
	v_pk_fma_f32 v[114:115], v[114:115], 2.0, 1.0 op_sel_hi:[1,0,0] neg_lo:[1,0,0] neg_hi:[1,0,0]
	v_mul_f32_e32 v38, 0x3fb8aa3b, v38
	v_pk_add_f32 v[114:115], v[114:115], 1.0 op_sel_hi:[1,0]
	v_exp_f32_e32 v102, v38
	v_pk_mul_f32 v[48:49], v[48:49], v[114:115]
	v_mul_f32_e32 v38, 0x3fb8aa3b, v39
	v_pk_mul_f32 v[6:7], v[48:49], v[6:7]
	v_exp_f32_e32 v103, v38
	v_cvt_pk_bf16_f32 v3, v6, v7
	v_pk_fma_f32 v[6:7], v[112:113], v[30:31], v[110:111]
	v_lshlrev_b32_e32 v30, 16, v23
	v_mul_f32_e32 v18, 0x3d372713, v30
	v_and_b32_e32 v31, 0xffff0000, v23
	v_mul_f32_e32 v18, v18, v30
	v_mov_b32_e32 v23, v30
	v_fmac_f32_e32 v23, v18, v23
	v_mul_f32_e32 v18, 0x3f4c422a, v23
	v_add_f32_e32 v18, v18, v18
	v_mul_f32_e32 v18, 0x3fb8aa3b, v18
	v_exp_f32_e32 v18, v18
	v_mov_b32_e32 v23, v31
	v_pk_add_f32 v[26:27], v[6:7], v[26:27]
	v_cvt_pk_f32_fp8_sdwa v[90:91], v89 src0_sel:WORD_1
	v_add_f32_e32 v18, 1.0, v18
	v_rcp_f32_e32 v48, v18
	v_mul_f32_e32 v18, 0x3d372713, v31
	v_mul_f32_e32 v18, v18, v31
	v_fmac_f32_e32 v23, v18, v23
	v_mul_f32_e32 v18, 0x3f4c422a, v23
	v_add_f32_e32 v18, v18, v18
	v_mul_f32_e32 v18, 0x3fb8aa3b, v18
	v_exp_f32_e32 v18, v18
	v_pk_mul_f32 v[30:31], v[30:31], 0.5 op_sel_hi:[1,0]
	v_pk_mul_f32 v[26:27], v[26:27], s[42:43] op_sel_hi:[1,0]
	v_lshlrev_b32_e32 v38, 16, v41
	v_add_f32_e32 v18, 1.0, v18
	v_rcp_f32_e32 v49, v18
	v_lshlrev_b32_e32 v18, 16, v11
	v_and_b32_e32 v39, 0xffff0000, v41
	v_mul_f32_e32 v38, 0x3fb8aa3b, v38
	v_pk_fma_f32 v[48:49], v[48:49], 2.0, 1.0 op_sel_hi:[1,0,0] neg_lo:[1,0,0] neg_hi:[1,0,0]
	v_exp_f32_e32 v88, v38
	v_pk_add_f32 v[48:49], v[48:49], 1.0 op_sel_hi:[1,0]
	v_mul_f32_e32 v38, 0x3fb8aa3b, v39
	v_pk_mul_f32 v[30:31], v[30:31], v[48:49]
	v_pk_fma_f32 v[48:49], v[34:35], v[6:7], v[108:109]
	v_pk_mul_f32 v[26:27], v[30:31], v[26:27]
	v_lshlrev_b32_e32 v6, 16, v19
	v_and_b32_e32 v7, 0xffff0000, v19
	v_and_b32_e32 v19, 0xffff0000, v11
	v_mul_f32_e32 v11, 0x3d372713, v18
	v_cvt_pk_bf16_f32 v23, v26, v27
	v_mul_f32_e32 v11, v11, v18
	v_mov_b32_e32 v26, v18
	v_fmac_f32_e32 v26, v11, v26
	v_mul_f32_e32 v11, 0x3f4c422a, v26
	v_add_f32_e32 v11, v11, v11
	v_mul_f32_e32 v11, 0x3fb8aa3b, v11
	v_exp_f32_e32 v11, v11
	v_mov_b32_e32 v27, v19
	v_lshlrev_b32_e32 v30, 16, v16
	v_and_b32_e32 v31, 0xffff0000, v16
	v_add_f32_e32 v11, 1.0, v11
	v_rcp_f32_e32 v26, v11
	v_mul_f32_e32 v11, 0x3d372713, v19
	v_mul_f32_e32 v11, v11, v19
	v_fmac_f32_e32 v27, v11, v27
	v_mul_f32_e32 v11, 0x3f4c422a, v27
	v_add_f32_e32 v11, v11, v11
	v_mul_f32_e32 v11, 0x3fb8aa3b, v11
	v_exp_f32_e32 v11, v11
	v_pk_mul_f32 v[18:19], v[18:19], 0.5 op_sel_hi:[1,0]
	v_mul_f32_e32 v16, 0x3d372713, v30
	v_mul_f32_e32 v16, v16, v30
	v_add_f32_e32 v11, 1.0, v11
	v_rcp_f32_e32 v27, v11
	v_pk_add_f32 v[6:7], v[48:49], v[6:7]
	v_exp_f32_e32 v89, v38
	v_pk_mul_f32 v[6:7], v[6:7], s[42:43] op_sel_hi:[1,0]
	v_pk_fma_f32 v[26:27], v[26:27], 2.0, 1.0 op_sel_hi:[1,0,0] neg_lo:[1,0,0] neg_hi:[1,0,0]
	v_add_u32_e32 v66, 0xfffff800, v54
	v_pk_add_f32 v[26:27], v[26:27], 1.0 op_sel_hi:[1,0]
	v_lshl_add_u64 v[38:39], s[26:27], 0, v[66:67]
	v_pk_mul_f32 v[18:19], v[18:19], v[26:27]
	v_lshlrev_b32_e32 v26, 16, v32
	v_and_b32_e32 v27, 0xffff0000, v32
	v_mov_b32_e32 v32, v30
	v_fmac_f32_e32 v32, v16, v32
	v_mul_f32_e32 v16, 0x3f4c422a, v32
	v_add_f32_e32 v16, v16, v16
	v_mul_f32_e32 v16, 0x3fb8aa3b, v16
	v_exp_f32_e32 v16, v16
	v_mov_b32_e32 v32, v31
	v_pk_mul_f32 v[6:7], v[18:19], v[6:7]
	v_pk_fma_f32 v[18:19], v[46:47], v[106:107], v[104:105]
	v_add_f32_e32 v16, 1.0, v16
	v_rcp_f32_e32 v34, v16
	v_mul_f32_e32 v16, 0x3d372713, v31
	v_mul_f32_e32 v16, v16, v31
	v_fmac_f32_e32 v32, v16, v32
	v_mul_f32_e32 v16, 0x3f4c422a, v32
	v_add_f32_e32 v16, v16, v16
	v_mul_f32_e32 v16, 0x3fb8aa3b, v16
	v_exp_f32_e32 v16, v16
	v_pk_mul_f32 v[30:31], v[30:31], 0.5 op_sel_hi:[1,0]
	v_pk_add_f32 v[26:27], v[18:19], v[26:27]
	v_pk_fma_f32 v[18:19], v[102:103], v[18:19], v[100:101]
	v_add_f32_e32 v16, 1.0, v16
	v_rcp_f32_e32 v35, v16
	v_pk_mul_f32 v[26:27], v[26:27], s[42:43] op_sel_hi:[1,0]
	v_cvt_pk_bf16_f32 v11, v6, v7
	v_lshlrev_b32_e32 v6, 16, v36
	v_pk_fma_f32 v[34:35], v[34:35], 2.0, 1.0 op_sel_hi:[1,0,0] neg_lo:[1,0,0] neg_hi:[1,0,0]
	v_and_b32_e32 v7, 0xffff0000, v36
	v_pk_add_f32 v[34:35], v[34:35], 1.0 op_sel_hi:[1,0]
	v_mul_f32_e32 v6, 0x3fb8aa3b, v6
	v_pk_mul_f32 v[30:31], v[30:31], v[34:35]
	v_mul_f32_e32 v7, 0x3fb8aa3b, v7
	v_pk_mul_f32 v[26:27], v[30:31], v[26:27]
	v_lshlrev_b32_e32 v30, 16, v4
	v_and_b32_e32 v31, 0xffff0000, v4
	v_mul_f32_e32 v4, 0x3d372713, v30
	v_cvt_pk_bf16_f32 v16, v26, v27
	v_lshlrev_b32_e32 v26, 16, v8
	v_and_b32_e32 v27, 0xffff0000, v8
	v_mul_f32_e32 v4, v4, v30
	v_mov_b32_e32 v8, v30
	v_fmac_f32_e32 v8, v4, v8
	v_mul_f32_e32 v4, 0x3f4c422a, v8
	v_add_f32_e32 v4, v4, v4
	v_mul_f32_e32 v4, 0x3fb8aa3b, v4
	v_exp_f32_e32 v4, v4
	v_mov_b32_e32 v8, v31
	v_pk_add_f32 v[26:27], v[18:19], v[26:27]
	v_exp_f32_e32 v6, v6
	v_add_f32_e32 v4, 1.0, v4
	v_rcp_f32_e32 v34, v4
	v_mul_f32_e32 v4, 0x3d372713, v31
	v_mul_f32_e32 v4, v4, v31
	v_fmac_f32_e32 v8, v4, v8
	v_mul_f32_e32 v4, 0x3f4c422a, v8
	v_add_f32_e32 v4, v4, v4
	v_mul_f32_e32 v4, 0x3fb8aa3b, v4
	v_exp_f32_e32 v4, v4
	v_pk_mul_f32 v[30:31], v[30:31], 0.5 op_sel_hi:[1,0]
	v_pk_mul_f32 v[26:27], v[26:27], s[42:43] op_sel_hi:[1,0]
	v_exp_f32_e32 v7, v7
	v_add_f32_e32 v4, 1.0, v4
	v_rcp_f32_e32 v35, v4
	v_pk_fma_f32 v[18:19], v[98:99], v[18:19], v[96:97]
	v_lshl_add_u32 v66, s6, 11, v68
	v_pk_fma_f32 v[46:47], v[6:7], v[18:19], v[94:95]
	v_pk_fma_f32 v[34:35], v[34:35], 2.0, 1.0 op_sel_hi:[1,0,0] neg_lo:[1,0,0] neg_hi:[1,0,0]
	v_lshlrev_b32_e32 v6, 16, v20
	v_pk_add_f32 v[34:35], v[34:35], 1.0 op_sel_hi:[1,0]
	v_and_b32_e32 v7, 0xffff0000, v20
	v_pk_mul_f32 v[30:31], v[30:31], v[34:35]
	v_pk_add_f32 v[6:7], v[46:47], v[6:7]
	v_pk_mul_f32 v[26:27], v[30:31], v[26:27]
	v_lshlrev_b32_e32 v30, 16, v24
	v_mul_f32_e32 v8, 0x3d372713, v30
	v_and_b32_e32 v31, 0xffff0000, v24
	v_mul_f32_e32 v8, v8, v30
	v_mov_b32_e32 v24, v30
	v_fmac_f32_e32 v24, v8, v24
	v_mul_f32_e32 v8, 0x3f4c422a, v24
	v_add_f32_e32 v8, v8, v8
	v_mul_f32_e32 v8, 0x3fb8aa3b, v8
	v_exp_f32_e32 v8, v8
	v_mov_b32_e32 v24, v31
	v_cvt_pk_bf16_f32 v4, v26, v27
	v_lshlrev_b32_e32 v26, 16, v28
	v_add_f32_e32 v8, 1.0, v8
	v_rcp_f32_e32 v34, v8
	v_mul_f32_e32 v8, 0x3d372713, v31
	v_mul_f32_e32 v8, v8, v31
	v_fmac_f32_e32 v24, v8, v24
	v_mul_f32_e32 v8, 0x3f4c422a, v24
	v_add_f32_e32 v8, v8, v8
	v_mul_f32_e32 v8, 0x3fb8aa3b, v8
	v_exp_f32_e32 v8, v8
	v_and_b32_e32 v27, 0xffff0000, v28
	v_pk_add_f32 v[26:27], v[18:19], v[26:27]
	v_lshlrev_b32_e32 v18, 16, v12
	v_add_f32_e32 v8, 1.0, v8
	v_rcp_f32_e32 v35, v8
	v_mul_f32_e32 v8, 0x3d372713, v18
	v_and_b32_e32 v19, 0xffff0000, v12
	v_mul_f32_e32 v8, v8, v18
	v_mov_b32_e32 v12, v18
	v_fmac_f32_e32 v12, v8, v12
	v_mul_f32_e32 v8, 0x3f4c422a, v12
	v_add_f32_e32 v8, v8, v8
	v_mul_f32_e32 v8, 0x3fb8aa3b, v8
	v_exp_f32_e32 v8, v8
	v_pk_fma_f32 v[34:35], v[34:35], 2.0, 1.0 op_sel_hi:[1,0,0] neg_lo:[1,0,0] neg_hi:[1,0,0]
	v_pk_mul_f32 v[30:31], v[30:31], 0.5 op_sel_hi:[1,0]
	v_pk_add_f32 v[34:35], v[34:35], 1.0 op_sel_hi:[1,0]
	v_pk_mul_f32 v[26:27], v[26:27], s[42:43] op_sel_hi:[1,0]
	v_pk_mul_f32 v[30:31], v[30:31], v[34:35]
	v_add_f32_e32 v8, 1.0, v8
	v_pk_mul_f32 v[26:27], v[30:31], v[26:27]
	v_mov_b32_e32 v12, v19
	v_cvt_pk_bf16_f32 v24, v26, v27
	v_rcp_f32_e32 v26, v8
	v_mul_f32_e32 v8, 0x3d372713, v19
	v_mul_f32_e32 v8, v8, v19
	v_fmac_f32_e32 v12, v8, v12
	v_mul_f32_e32 v8, 0x3f4c422a, v12
	v_add_f32_e32 v8, v8, v8
	v_mul_f32_e32 v8, 0x3fb8aa3b, v8
	v_exp_f32_e32 v8, v8
	v_lshlrev_b32_e32 v30, 16, v17
	v_and_b32_e32 v31, 0xffff0000, v17
	v_mov_b32_e32 v17, v30
	v_add_f32_e32 v8, 1.0, v8
	v_rcp_f32_e32 v27, v8
	v_mul_f32_e32 v8, 0x3d372713, v30
	v_mul_f32_e32 v8, v8, v30
	v_fmac_f32_e32 v17, v8, v17
	v_mul_f32_e32 v8, 0x3f4c422a, v17
	v_add_f32_e32 v8, v8, v8
	v_mul_f32_e32 v8, 0x3fb8aa3b, v8
	v_exp_f32_e32 v8, v8
	v_mov_b32_e32 v17, v31
	v_pk_fma_f32 v[26:27], v[26:27], 2.0, 1.0 op_sel_hi:[1,0,0] neg_lo:[1,0,0] neg_hi:[1,0,0]
	v_pk_mul_f32 v[18:19], v[18:19], 0.5 op_sel_hi:[1,0]
	v_add_f32_e32 v8, 1.0, v8
	v_rcp_f32_e32 v32, v8
	v_mul_f32_e32 v8, 0x3d372713, v31
	v_mul_f32_e32 v8, v8, v31
	v_fmac_f32_e32 v17, v8, v17
	v_mul_f32_e32 v8, 0x3f4c422a, v17
	v_add_f32_e32 v8, v8, v8
	v_mul_f32_e32 v8, 0x3fb8aa3b, v8
	v_exp_f32_e32 v8, v8
	v_pk_add_f32 v[26:27], v[26:27], 1.0 op_sel_hi:[1,0]
	v_pk_mul_f32 v[6:7], v[6:7], s[42:43] op_sel_hi:[1,0]
	v_pk_mul_f32 v[18:19], v[18:19], v[26:27]
	v_add_f32_e32 v8, 1.0, v8
	v_pk_mul_f32 v[6:7], v[18:19], v[6:7]
	v_lshlrev_b32_e32 v26, 16, v33
	v_and_b32_e32 v27, 0xffff0000, v33
	v_rcp_f32_e32 v33, v8
	v_cvt_pk_bf16_f32 v12, v6, v7
	v_lshlrev_b32_e32 v6, 16, v37
	v_and_b32_e32 v7, 0xffff0000, v37
	v_mul_f32_e32 v6, 0x3fb8aa3b, v6
	v_exp_f32_e32 v18, v6
	v_mul_f32_e32 v6, 0x3fb8aa3b, v7
	v_exp_f32_e32 v19, v6
	v_pk_fma_f32 v[6:7], v[52:53], v[92:93], v[90:91]
	v_pk_fma_f32 v[32:33], v[32:33], 2.0, 1.0 op_sel_hi:[1,0,0] neg_lo:[1,0,0] neg_hi:[1,0,0]
	v_pk_mul_f32 v[30:31], v[30:31], 0.5 op_sel_hi:[1,0]
	v_pk_add_f32 v[32:33], v[32:33], 1.0 op_sel_hi:[1,0]
	v_pk_add_f32 v[26:27], v[6:7], v[26:27]
	v_pk_mul_f32 v[30:31], v[30:31], v[32:33]
	v_pk_mul_f32 v[26:27], v[26:27], s[42:43] op_sel_hi:[1,0]
	v_lshlrev_b32_e32 v8, 16, v5
	v_pk_mul_f32 v[26:27], v[30:31], v[26:27]
	v_lshl_add_u64 v[40:41], s[20:21], 0, v[66:67]
	v_cvt_pk_bf16_f32 v17, v26, v27
	v_pk_fma_f32 v[26:27], v[88:89], v[6:7], v[44:45]
	v_lshlrev_b32_e32 v6, 16, v9
	v_and_b32_e32 v7, 0xffff0000, v9
	v_and_b32_e32 v9, 0xffff0000, v5
	v_mul_f32_e32 v5, 0x3d372713, v8
	global_store_dwordx4 v[42:43], v[14:17], off
	v_mul_f32_e32 v5, v5, v8
	v_pk_add_f32 v[6:7], v[26:27], v[6:7]
	v_mov_b32_e32 v14, v8
	v_fmac_f32_e32 v14, v5, v14
	v_mul_f32_e32 v5, 0x3f4c422a, v14
	v_add_f32_e32 v5, v5, v5
	v_mul_f32_e32 v5, 0x3fb8aa3b, v5
	v_exp_f32_e32 v5, v5
	v_mov_b32_e32 v15, v9
	v_pk_mul_f32 v[6:7], v[6:7], s[42:43] op_sel_hi:[1,0]
	v_lshl_add_u64 v[76:77], s[30:31], 0, v[66:67]
	v_add_f32_e32 v5, 1.0, v5
	v_rcp_f32_e32 v14, v5
	v_mul_f32_e32 v5, 0x3d372713, v9
	v_mul_f32_e32 v5, v5, v9
	v_fmac_f32_e32 v15, v5, v15
	v_mul_f32_e32 v5, 0x3f4c422a, v15
	v_add_f32_e32 v5, v5, v5
	v_mul_f32_e32 v5, 0x3fb8aa3b, v5
	v_exp_f32_e32 v5, v5
	v_pk_mul_f32 v[8:9], v[8:9], 0.5 op_sel_hi:[1,0]
	v_lshl_add_u64 v[78:79], s[26:27], 0, v[66:67]
	v_lshl_add_u32 v66, s1, 11, v68
	v_add_f32_e32 v5, 1.0, v5
	v_rcp_f32_e32 v15, v5
	v_lshl_add_u64 v[80:81], s[20:21], 0, v[66:67]
	v_lshl_add_u64 v[84:85], s[30:31], 0, v[66:67]
	v_lshl_add_u64 v[86:87], s[26:27], 0, v[66:67]
	v_pk_fma_f32 v[14:15], v[14:15], 2.0, 1.0 op_sel_hi:[1,0,0] neg_lo:[1,0,0] neg_hi:[1,0,0]
	v_pk_fma_f32 v[126:127], v[126:127], 2.0, 1.0 op_sel_hi:[1,0,0] neg_lo:[1,0,0] neg_hi:[1,0,0]
	v_pk_add_f32 v[14:15], v[14:15], 1.0 op_sel_hi:[1,0]
	v_pk_mul_f32 v[124:125], v[124:125], 0.5 op_sel_hi:[1,0]
	v_pk_mul_f32 v[8:9], v[8:9], v[14:15]
	v_pk_add_f32 v[126:127], v[126:127], 1.0 op_sel_hi:[1,0]
	v_pk_mul_f32 v[6:7], v[8:9], v[6:7]
	v_pk_add_f32 v[122:123], v[50:51], v[122:123]
	v_cvt_pk_bf16_f32 v5, v6, v7
	global_store_dwordx4 v[38:39], v[2:5], off
	global_load_dwordx4 v[42:45], v[40:41], off
	global_load_dwordx2 v[88:89], v[74:75], off
	global_load_dwordx4 v[30:33], v[76:77], off
	global_load_dwordx4 v[14:17], v[78:79], off
	s_nop 0
	global_load_dwordx4 v[38:41], v[80:81], off
	global_load_dwordx2 v[74:75], v[82:83], off
	global_load_dwordx4 v[6:9], v[84:85], off
	global_load_dwordx4 v[2:5], v[86:87], off
	v_pk_mul_f32 v[124:125], v[124:125], v[126:127]
	v_pk_mul_f32 v[122:123], v[122:123], s[42:43] op_sel_hi:[1,0]
	s_add_i32 s4, s4, 4
	v_pk_mul_f32 v[122:123], v[124:125], v[122:123]
	s_cmp_gt_u32 s0, 29
	v_cvt_pk_bf16_f32 v10, v122, v123
	v_lshlrev_b32_e32 v34, 16, v25
	v_mul_f32_e32 v20, 0x3d372713, v34
	v_and_b32_e32 v35, 0xffff0000, v25
	v_mul_f32_e32 v20, v20, v34
	v_mov_b32_e32 v25, v34
	v_fmac_f32_e32 v25, v20, v25
	v_mul_f32_e32 v20, 0x3f4c422a, v25
	v_add_f32_e32 v20, v20, v20
	v_mul_f32_e32 v20, 0x3fb8aa3b, v20
	v_exp_f32_e32 v20, v20
	v_mov_b32_e32 v25, v35
	v_pk_fma_f32 v[26:27], v[72:73], v[26:27], v[64:65]
	v_lshlrev_b32_e32 v28, 16, v29
	v_add_f32_e32 v20, 1.0, v20
	v_rcp_f32_e32 v36, v20
	v_mul_f32_e32 v20, 0x3d372713, v35
	v_mul_f32_e32 v20, v20, v35
	v_fmac_f32_e32 v25, v20, v25
	v_mul_f32_e32 v20, 0x3f4c422a, v25
	v_add_f32_e32 v20, v20, v20
	v_mul_f32_e32 v20, 0x3fb8aa3b, v20
	v_exp_f32_e32 v20, v20
	v_and_b32_e32 v29, 0xffff0000, v29
	v_pk_mul_f32 v[34:35], v[34:35], 0.5 op_sel_hi:[1,0]
	v_pk_add_f32 v[28:29], v[26:27], v[28:29]
	v_add_f32_e32 v20, 1.0, v20
	v_rcp_f32_e32 v37, v20
	v_pk_mul_f32 v[28:29], v[28:29], s[42:43] op_sel_hi:[1,0]
	v_lshlrev_b32_e32 v20, 16, v13
	v_pk_fma_f32 v[52:53], v[18:19], v[26:27], v[62:63]
	v_pk_fma_f32 v[36:37], v[36:37], 2.0, 1.0 op_sel_hi:[1,0,0] neg_lo:[1,0,0] neg_hi:[1,0,0]
	v_lshlrev_b32_e32 v18, 16, v21
	v_pk_add_f32 v[36:37], v[36:37], 1.0 op_sel_hi:[1,0]
	v_and_b32_e32 v19, 0xffff0000, v21
	v_pk_mul_f32 v[34:35], v[34:35], v[36:37]
	v_and_b32_e32 v21, 0xffff0000, v13
	v_pk_mul_f32 v[28:29], v[34:35], v[28:29]
	v_mul_f32_e32 v13, 0x3d372713, v20
	v_cvt_pk_bf16_f32 v25, v28, v29
	global_store_dwordx4 v[60:61], v[22:25], off
	v_mul_f32_e32 v13, v13, v20
	v_pk_add_f32 v[18:19], v[52:53], v[18:19]
	v_mov_b32_e32 v22, v20
	v_fmac_f32_e32 v22, v13, v22
	v_mul_f32_e32 v13, 0x3f4c422a, v22
	v_add_f32_e32 v13, v13, v13
	v_mul_f32_e32 v13, 0x3fb8aa3b, v13
	v_exp_f32_e32 v13, v13
	v_mov_b32_e32 v23, v21
	v_pk_mul_f32 v[18:19], v[18:19], s[42:43] op_sel_hi:[1,0]
	s_movk_i32 s0, 0xf000
	v_add_f32_e32 v13, 1.0, v13
	v_rcp_f32_e32 v22, v13
	v_mul_f32_e32 v13, 0x3d372713, v21
	v_mul_f32_e32 v13, v13, v21
	v_fmac_f32_e32 v23, v13, v23
	v_mul_f32_e32 v13, 0x3f4c422a, v23
	v_add_f32_e32 v13, v13, v13
	v_mul_f32_e32 v13, 0x3fb8aa3b, v13
	v_exp_f32_e32 v13, v13
	v_pk_mul_f32 v[20:21], v[20:21], 0.5 op_sel_hi:[1,0]
	s_mov_b32 s1, -1
	v_add_u32_e32 v54, 0xffffe000, v54
	v_add_f32_e32 v13, 1.0, v13
	v_rcp_f32_e32 v23, v13
	v_lshl_add_u64 v[56:57], v[56:57], 0, s[0:1]
	s_mov_b32 s0, s5
	v_pk_fma_f32 v[22:23], v[22:23], 2.0, 1.0 op_sel_hi:[1,0,0] neg_lo:[1,0,0] neg_hi:[1,0,0]
	s_nop 0
	v_pk_add_f32 v[22:23], v[22:23], 1.0 op_sel_hi:[1,0]
	s_nop 0
	v_pk_mul_f32 v[20:21], v[20:21], v[22:23]
	s_nop 0
	v_pk_mul_f32 v[18:19], v[20:21], v[18:19]
	s_nop 0
	v_cvt_pk_bf16_f32 v13, v18, v19
	global_store_dwordx4 v[58:59], v[10:13], off
	s_cbranch_scc0 .LBB0_1726
	s_add_i32 s52, s52, s74
	s_add_i32 s50, s50, s51
	s_cmpk_gt_i32 s52, 0xff
	s_waitcnt lgkmcnt(0)
	s_barrier
	s_cbranch_scc0 .LBB0_1705

.LBB0_1786:
	ds_read_b128 v[130:133], v168
	ds_read_b128 v[134:137], v168 offset:1024
	ds_read_b128 v[138:141], v168 offset:2048
	ds_read_b128 v[142:145], v168 offset:3072
	s_add_u32 s0, s38, 0xfffc0080
	s_addc_u32 s1, s39, -1
	s_cmp_eq_u32 s66, 12
	s_cselect_b32 s43, s60, s1
	s_cselect_b32 s42, s61, s0
	s_cselect_b32 s41, s62, s65
	s_cselect_b32 s40, s63, s64
	s_mov_b32 m0, s50
	v_lshl_add_u64 v[164:165], s[38:39], 0, v[162:163]
	ds_read_b128 v[146:149], v169
	ds_read_b128 v[172:175], v169 offset:1024
	ds_read_b128 v[176:179], v169 offset:2048
	ds_read_b128 v[180:183], v169 offset:3072
	ds_read_b128 v[184:187], v169 offset:4096
	ds_read_b128 v[188:191], v169 offset:5120
	ds_read_b128 v[192:195], v169 offset:6144
	ds_read_b128 v[196:199], v169 offset:7168
	global_load_lds_dwordx4 v[164:165], off
	v_lshl_add_u64 v[164:165], s[38:39], 0, v[160:161]
	s_mov_b32 m0, s51
	s_nop 0
	global_load_lds_dwordx4 v[164:165], off
	s_waitcnt lgkmcnt(8)
	s_waitcnt vmcnt(10)
	s_barrier
	s_waitcnt lgkmcnt(0)
	s_waitcnt lgkmcnt(0)
	v_mfma_f32_16x16x32_bf16 v[126:129], v[130:133], v[146:149], v[126:129]
	v_mfma_f32_16x16x32_bf16 v[122:125], v[138:141], v[146:149], v[122:125]
	v_mfma_f32_16x16x32_bf16 v[118:121], v[130:133], v[176:179], v[118:121]
	v_mfma_f32_16x16x32_bf16 v[110:113], v[138:141], v[176:179], v[110:113]
	v_mfma_f32_16x16x32_bf16 v[98:101], v[130:133], v[184:187], v[98:101]
	v_mfma_f32_16x16x32_bf16 v[90:93], v[138:141], v[184:187], v[90:93]
	v_mfma_f32_16x16x32_bf16 v[82:85], v[130:133], v[192:195], v[82:85]
	v_mfma_f32_16x16x32_bf16 v[74:77], v[138:141], v[192:195], v[74:77]
	v_mfma_f32_16x16x32_bf16 v[126:129], v[134:137], v[172:175], v[126:129]
	v_mfma_f32_16x16x32_bf16 v[122:125], v[142:145], v[172:175], v[122:125]
	v_mfma_f32_16x16x32_bf16 v[118:121], v[134:137], v[180:183], v[118:121]
	v_mfma_f32_16x16x32_bf16 v[110:113], v[142:145], v[180:183], v[110:113]
	v_mfma_f32_16x16x32_bf16 v[98:101], v[134:137], v[188:191], v[98:101]
	v_mfma_f32_16x16x32_bf16 v[90:93], v[142:145], v[188:191], v[90:93]
	v_mfma_f32_16x16x32_bf16 v[82:85], v[134:137], v[196:199], v[82:85]
	v_mfma_f32_16x16x32_bf16 v[74:77], v[142:145], v[196:199], v[74:77]
	s_barrier
	s_mov_b32 m0, s52
	v_lshl_add_u64 v[164:165], s[40:41], 0, v[156:157]
	ds_read_b128 v[200:203], v170
	ds_read_b128 v[204:207], v170 offset:1024
	ds_read_b128 v[208:211], v170 offset:2048
	ds_read_b128 v[212:215], v170 offset:3072
	global_load_lds_dwordx4 v[164:165], off
	v_lshl_add_u64 v[216:217], s[40:41], 0, v[152:153]
	s_mov_b32 m0, s53
	s_nop 0
	global_load_lds_dwordx4 v[216:217], off
	s_waitcnt vmcnt(10)
	s_barrier
	s_waitcnt lgkmcnt(0)
	s_waitcnt lgkmcnt(0)
	v_mfma_f32_16x16x32_bf16 v[114:117], v[200:203], v[146:149], v[114:117]
	v_mfma_f32_16x16x32_bf16 v[106:109], v[208:211], v[146:149], v[106:109]
	v_mfma_f32_16x16x32_bf16 v[102:105], v[200:203], v[176:179], v[102:105]
	v_mfma_f32_16x16x32_bf16 v[94:97], v[208:211], v[176:179], v[94:97]
	v_mfma_f32_16x16x32_bf16 v[86:89], v[200:203], v[184:187], v[86:89]
	v_mfma_f32_16x16x32_bf16 v[78:81], v[208:211], v[184:187], v[78:81]
	v_mfma_f32_16x16x32_bf16 v[70:73], v[200:203], v[192:195], v[70:73]
	v_mfma_f32_16x16x32_bf16 v[66:69], v[208:211], v[192:195], v[66:69]
	v_mfma_f32_16x16x32_bf16 v[114:117], v[204:207], v[172:175], v[114:117]
	v_mfma_f32_16x16x32_bf16 v[106:109], v[212:215], v[172:175], v[106:109]
	v_mfma_f32_16x16x32_bf16 v[102:105], v[204:207], v[180:183], v[102:105]
	v_mfma_f32_16x16x32_bf16 v[94:97], v[212:215], v[180:183], v[94:97]
	v_mfma_f32_16x16x32_bf16 v[86:89], v[204:207], v[188:191], v[86:89]
	v_mfma_f32_16x16x32_bf16 v[78:81], v[212:215], v[188:191], v[78:81]
	v_mfma_f32_16x16x32_bf16 v[70:73], v[204:207], v[196:199], v[70:73]
	v_mfma_f32_16x16x32_bf16 v[66:69], v[212:215], v[196:199], v[66:69]
	s_mov_b32 m0, s8
	v_lshl_add_u64 v[218:219], s[42:43], 0, v[158:159]
	s_barrier
	ds_read_b128 v[146:149], v169 offset:16384
	ds_read_b128 v[172:175], v169 offset:17408
	ds_read_b128 v[176:179], v169 offset:18432
	ds_read_b128 v[180:183], v169 offset:19456
	ds_read_b128 v[184:187], v169 offset:20480
	ds_read_b128 v[188:191], v169 offset:21504
	ds_read_b128 v[192:195], v169 offset:22528
	ds_read_b128 v[196:199], v169 offset:23552
	global_load_lds_dwordx4 v[218:219], off
	v_lshl_add_u64 v[220:221], s[42:43], 0, v[154:155]
	s_mov_b32 m0, s9
	s_nop 0
	global_load_lds_dwordx4 v[220:221], off
	s_waitcnt vmcnt(10)
	s_barrier
	s_waitcnt lgkmcnt(0)
	s_waitcnt lgkmcnt(0)
	v_mfma_f32_16x16x32_bf16 v[62:65], v[130:133], v[146:149], v[62:65]
	v_mfma_f32_16x16x32_bf16 v[58:61], v[138:141], v[146:149], v[58:61]
	v_mfma_f32_16x16x32_bf16 v[50:53], v[130:133], v[176:179], v[50:53]
	v_mfma_f32_16x16x32_bf16 v[42:45], v[138:141], v[176:179], v[42:45]
	v_mfma_f32_16x16x32_bf16 v[34:37], v[130:133], v[184:187], v[34:37]
	v_mfma_f32_16x16x32_bf16 v[26:29], v[138:141], v[184:187], v[26:29]
	v_mfma_f32_16x16x32_bf16 v[18:21], v[130:133], v[192:195], v[18:21]
	v_mfma_f32_16x16x32_bf16 v[10:13], v[138:141], v[192:195], v[10:13]
	v_mfma_f32_16x16x32_bf16 v[62:65], v[134:137], v[172:175], v[62:65]
	v_mfma_f32_16x16x32_bf16 v[58:61], v[142:145], v[172:175], v[58:61]
	v_mfma_f32_16x16x32_bf16 v[50:53], v[134:137], v[180:183], v[50:53]
	v_mfma_f32_16x16x32_bf16 v[42:45], v[142:145], v[180:183], v[42:45]
	v_mfma_f32_16x16x32_bf16 v[34:37], v[134:137], v[188:191], v[34:37]
	v_mfma_f32_16x16x32_bf16 v[26:29], v[142:145], v[188:191], v[26:29]
	v_mfma_f32_16x16x32_bf16 v[18:21], v[134:137], v[196:199], v[18:21]
	v_mfma_f32_16x16x32_bf16 v[10:13], v[142:145], v[196:199], v[10:13]
	s_barrier
	s_add_u32 s0, s40, 0x40000
	s_addc_u32 s1, s41, 0
	s_mov_b32 m0, s54
	v_lshl_add_u64 v[130:131], s[0:1], 0, v[156:157]
	global_load_lds_dwordx4 v[130:131], off
	v_lshl_add_u64 v[130:131], s[0:1], 0, v[152:153]
	s_add_i32 m0, s54, 0x2000
	s_nop 0
	global_load_lds_dwordx4 v[130:131], off
	s_waitcnt vmcnt(10)
	s_barrier
	v_mfma_f32_16x16x32_bf16 v[54:57], v[200:203], v[146:149], v[54:57]
	v_mfma_f32_16x16x32_bf16 v[46:49], v[208:211], v[146:149], v[46:49]
	v_mfma_f32_16x16x32_bf16 v[38:41], v[200:203], v[176:179], v[38:41]
	v_mfma_f32_16x16x32_bf16 v[30:33], v[208:211], v[176:179], v[30:33]
	v_mfma_f32_16x16x32_bf16 v[22:25], v[200:203], v[184:187], v[22:25]
	v_mfma_f32_16x16x32_bf16 v[14:17], v[208:211], v[184:187], v[14:17]
	v_mfma_f32_16x16x32_bf16 v[6:9], v[200:203], v[192:195], v[6:9]
	v_mfma_f32_16x16x32_bf16 v[2:5], v[208:211], v[192:195], v[2:5]
	v_mfma_f32_16x16x32_bf16 v[54:57], v[204:207], v[172:175], v[54:57]
	v_mfma_f32_16x16x32_bf16 v[46:49], v[212:215], v[172:175], v[46:49]
	v_mfma_f32_16x16x32_bf16 v[38:41], v[204:207], v[180:183], v[38:41]
	v_mfma_f32_16x16x32_bf16 v[30:33], v[212:215], v[180:183], v[30:33]
	v_mfma_f32_16x16x32_bf16 v[22:25], v[204:207], v[188:191], v[22:25]
	v_mfma_f32_16x16x32_bf16 v[14:17], v[212:215], v[188:191], v[14:17]
	v_mfma_f32_16x16x32_bf16 v[6:9], v[204:207], v[196:199], v[6:9]
	v_mfma_f32_16x16x32_bf16 v[2:5], v[212:215], v[196:199], v[2:5]
	s_add_i32 s67, 0, 0x18000
	v_add_u32_e32 v142, s67, v167
	s_barrier
	ds_read_b128 v[130:133], v142
	ds_read_b128 v[134:137], v142 offset:1024
	ds_read_b128 v[138:141], v142 offset:2048
	ds_read_b128 v[142:145], v142 offset:3072
	s_add_u32 s0, s42, 0x40000
	s_addc_u32 s1, s43, 0
	s_mov_b32 m0, s10
	v_lshl_add_u64 v[200:201], s[0:1], 0, v[158:159]
	ds_read_b128 v[146:149], v169 offset:32768
	ds_read_b128 v[172:175], v169 offset:33792
	ds_read_b128 v[176:179], v169 offset:34816
	ds_read_b128 v[180:183], v169 offset:35840
	ds_read_b128 v[184:187], v169 offset:36864
	ds_read_b128 v[188:191], v169 offset:37888
	ds_read_b128 v[192:195], v169 offset:38912
	ds_read_b128 v[196:199], v169 offset:39936
	global_load_lds_dwordx4 v[200:201], off
	v_lshl_add_u64 v[200:201], s[0:1], 0, v[154:155]
	s_mov_b32 m0, s11
	s_nop 0
	global_load_lds_dwordx4 v[200:201], off
	s_waitcnt lgkmcnt(8)
	s_waitcnt vmcnt(10)
	s_barrier
	s_waitcnt lgkmcnt(0)
	s_waitcnt lgkmcnt(0)
	v_mfma_f32_16x16x32_bf16 v[126:129], v[130:133], v[146:149], v[126:129]
	v_mfma_f32_16x16x32_bf16 v[122:125], v[138:141], v[146:149], v[122:125]
	v_mfma_f32_16x16x32_bf16 v[118:121], v[130:133], v[176:179], v[118:121]
	v_mfma_f32_16x16x32_bf16 v[110:113], v[138:141], v[176:179], v[110:113]
	v_mfma_f32_16x16x32_bf16 v[98:101], v[130:133], v[184:187], v[98:101]
	v_mfma_f32_16x16x32_bf16 v[90:93], v[138:141], v[184:187], v[90:93]
	v_mfma_f32_16x16x32_bf16 v[82:85], v[130:133], v[192:195], v[82:85]
	v_mfma_f32_16x16x32_bf16 v[74:77], v[138:141], v[192:195], v[74:77]
	v_mfma_f32_16x16x32_bf16 v[126:129], v[134:137], v[172:175], v[126:129]
	v_mfma_f32_16x16x32_bf16 v[122:125], v[142:145], v[172:175], v[122:125]
	v_mfma_f32_16x16x32_bf16 v[118:121], v[134:137], v[180:183], v[118:121]
	v_mfma_f32_16x16x32_bf16 v[110:113], v[142:145], v[180:183], v[110:113]
	v_mfma_f32_16x16x32_bf16 v[98:101], v[134:137], v[188:191], v[98:101]
	v_mfma_f32_16x16x32_bf16 v[90:93], v[142:145], v[188:191], v[90:93]
	v_mfma_f32_16x16x32_bf16 v[82:85], v[134:137], v[196:199], v[82:85]
	v_mfma_f32_16x16x32_bf16 v[74:77], v[142:145], v[196:199], v[74:77]
	s_barrier
	s_add_i32 s42, 0, 0x1c000
	s_add_i32 s0, s67, s7
	v_add_u32_e32 v171, s42, v167
	v_lshl_add_u64 v[164:165], v[164:165], 0, s[28:29]
	s_mov_b32 m0, s0
	ds_read_b128 v[200:203], v171
	ds_read_b128 v[204:207], v171 offset:1024
	ds_read_b128 v[208:211], v171 offset:2048
	ds_read_b128 v[212:215], v171 offset:3072
	global_load_lds_dwordx4 v[164:165], off
	v_lshl_add_u64 v[164:165], v[216:217], 0, s[28:29]
	s_add_i32 m0, s0, 0x2000
	s_nop 0
	global_load_lds_dwordx4 v[164:165], off
	s_waitcnt vmcnt(10)
	s_barrier
	s_waitcnt lgkmcnt(0)
	s_waitcnt lgkmcnt(0)
	v_mfma_f32_16x16x32_bf16 v[114:117], v[200:203], v[146:149], v[114:117]
	v_mfma_f32_16x16x32_bf16 v[106:109], v[208:211], v[146:149], v[106:109]
	v_mfma_f32_16x16x32_bf16 v[102:105], v[200:203], v[176:179], v[102:105]
	v_mfma_f32_16x16x32_bf16 v[94:97], v[208:211], v[176:179], v[94:97]
	v_mfma_f32_16x16x32_bf16 v[86:89], v[200:203], v[184:187], v[86:89]
	v_mfma_f32_16x16x32_bf16 v[78:81], v[208:211], v[184:187], v[78:81]
	v_mfma_f32_16x16x32_bf16 v[70:73], v[200:203], v[192:195], v[70:73]
	v_mfma_f32_16x16x32_bf16 v[66:69], v[208:211], v[192:195], v[66:69]
	v_mfma_f32_16x16x32_bf16 v[114:117], v[204:207], v[172:175], v[114:117]
	v_mfma_f32_16x16x32_bf16 v[106:109], v[212:215], v[172:175], v[106:109]
	v_mfma_f32_16x16x32_bf16 v[102:105], v[204:207], v[180:183], v[102:105]
	v_mfma_f32_16x16x32_bf16 v[94:97], v[212:215], v[180:183], v[94:97]
	v_mfma_f32_16x16x32_bf16 v[86:89], v[204:207], v[188:191], v[86:89]
	v_mfma_f32_16x16x32_bf16 v[78:81], v[212:215], v[188:191], v[78:81]
	v_mfma_f32_16x16x32_bf16 v[70:73], v[204:207], v[196:199], v[70:73]
	v_mfma_f32_16x16x32_bf16 v[66:69], v[212:215], v[196:199], v[66:69]
	s_mov_b32 m0, s48
	v_lshl_add_u64 v[164:165], v[218:219], 0, s[28:29]
	s_barrier
	ds_read_b128 v[146:149], v169 offset:49152
	ds_read_b128 v[172:175], v169 offset:50176
	ds_read_b128 v[176:179], v169 offset:51200
	ds_read_b128 v[180:183], v169 offset:52224
	ds_read_b128 v[184:187], v169 offset:53248
	ds_read_b128 v[188:191], v169 offset:54272
	ds_read_b128 v[192:195], v169 offset:55296
	ds_read_b128 v[196:199], v169 offset:56320
	global_load_lds_dwordx4 v[164:165], off
	v_lshl_add_u64 v[164:165], v[220:221], 0, s[28:29]
	s_mov_b32 m0, s49
	s_nop 0
	global_load_lds_dwordx4 v[164:165], off
	s_waitcnt vmcnt(10)
	s_barrier
	s_waitcnt lgkmcnt(0)
	s_waitcnt lgkmcnt(0)
	v_mfma_f32_16x16x32_bf16 v[62:65], v[130:133], v[146:149], v[62:65]
	v_mfma_f32_16x16x32_bf16 v[58:61], v[138:141], v[146:149], v[58:61]
	v_mfma_f32_16x16x32_bf16 v[50:53], v[130:133], v[176:179], v[50:53]
	v_mfma_f32_16x16x32_bf16 v[42:45], v[138:141], v[176:179], v[42:45]
	v_mfma_f32_16x16x32_bf16 v[34:37], v[130:133], v[184:187], v[34:37]
	v_mfma_f32_16x16x32_bf16 v[26:29], v[138:141], v[184:187], v[26:29]
	v_mfma_f32_16x16x32_bf16 v[18:21], v[130:133], v[192:195], v[18:21]
	v_mfma_f32_16x16x32_bf16 v[10:13], v[138:141], v[192:195], v[10:13]
	v_mfma_f32_16x16x32_bf16 v[62:65], v[134:137], v[172:175], v[62:65]
	v_mfma_f32_16x16x32_bf16 v[58:61], v[142:145], v[172:175], v[58:61]
	v_mfma_f32_16x16x32_bf16 v[50:53], v[134:137], v[180:183], v[50:53]
	v_mfma_f32_16x16x32_bf16 v[42:45], v[142:145], v[180:183], v[42:45]
	v_mfma_f32_16x16x32_bf16 v[34:37], v[134:137], v[188:191], v[34:37]
	v_mfma_f32_16x16x32_bf16 v[26:29], v[142:145], v[188:191], v[26:29]
	v_mfma_f32_16x16x32_bf16 v[18:21], v[134:137], v[196:199], v[18:21]
	v_mfma_f32_16x16x32_bf16 v[10:13], v[142:145], v[196:199], v[10:13]
	s_barrier
	s_add_u32 s0, s40, 0x40080
	s_addc_u32 s1, s41, 0
	s_add_i32 s40, s42, s7
	v_lshl_add_u64 v[130:131], s[0:1], 0, v[156:157]
	s_mov_b32 m0, s40
	s_nop 0
	global_load_lds_dwordx4 v[130:131], off
	v_lshl_add_u64 v[130:131], s[0:1], 0, v[152:153]
	s_add_i32 m0, s40, 0x2000
	s_nop 0
	global_load_lds_dwordx4 v[130:131], off
	s_waitcnt vmcnt(10)
	s_barrier
	v_mfma_f32_16x16x32_bf16 v[54:57], v[200:203], v[146:149], v[54:57]
	v_mfma_f32_16x16x32_bf16 v[46:49], v[208:211], v[146:149], v[46:49]
	v_mfma_f32_16x16x32_bf16 v[38:41], v[200:203], v[176:179], v[38:41]
	v_mfma_f32_16x16x32_bf16 v[30:33], v[208:211], v[176:179], v[30:33]
	v_mfma_f32_16x16x32_bf16 v[22:25], v[200:203], v[184:187], v[22:25]
	v_mfma_f32_16x16x32_bf16 v[14:17], v[208:211], v[184:187], v[14:17]
	v_mfma_f32_16x16x32_bf16 v[6:9], v[200:203], v[192:195], v[6:9]
	v_mfma_f32_16x16x32_bf16 v[2:5], v[208:211], v[192:195], v[2:5]
	v_mfma_f32_16x16x32_bf16 v[54:57], v[204:207], v[172:175], v[54:57]
	v_mfma_f32_16x16x32_bf16 v[46:49], v[212:215], v[172:175], v[46:49]
	v_mfma_f32_16x16x32_bf16 v[38:41], v[204:207], v[180:183], v[38:41]
	v_mfma_f32_16x16x32_bf16 v[30:33], v[212:215], v[180:183], v[30:33]
	v_mfma_f32_16x16x32_bf16 v[22:25], v[204:207], v[188:191], v[22:25]
	v_mfma_f32_16x16x32_bf16 v[14:17], v[212:215], v[188:191], v[14:17]
	v_mfma_f32_16x16x32_bf16 v[6:9], v[204:207], v[196:199], v[6:9]
	v_mfma_f32_16x16x32_bf16 v[2:5], v[212:215], v[196:199], v[2:5]
	s_add_i32 s66, s66, 2
	s_add_u32 s64, s64, 0x100
	s_addc_u32 s65, s65, 0
	s_add_u32 s38, s38, 0x100
	s_addc_u32 s39, s39, 0
	s_cmp_gt_u32 s66, 13
	s_barrier
	s_cbranch_scc0 .LBB0_1786
	s_lshl_b32 s0, s58, 8
	v_mov_b32_e32 v130, v151
	v_mov_b32_e32 v131, v166
	s_or_b32 s0, s0, s45
	s_mov_b32 s58, s57
	v_lshl_add_u32 v164, v131, 3, s0
	s_lshl_b32 s0, s59, 8
	s_add_i32 s0, s0, s44
	v_add_u32_e32 v171, s0, v130
	v_mov_b32_e32 v130, v171
	v_ashrrev_i32_e32 v165, 31, v164
	v_ashrrev_i32_e32 v131, 31, v130
	v_lshlrev_b64 v[130:131], 10, v[130:131]
	v_lshl_add_u64 v[130:131], v[130:131], 0, v[164:165]
	v_lshlrev_b64 v[184:185], 1, v[130:131]
	v_lshl_add_u64 v[130:131], s[14:15], 0, v[184:185]
	global_load_dwordx4 v[172:175], v[130:131], off
	global_load_dwordx4 v[176:179], v[130:131], off offset:256
	v_add_co_u32_e32 v132, vcc, s47, v130
	s_mov_b32 s59, s56
	s_nop 0
	v_addc_co_u32_e32 v133, vcc, 0, v131, vcc
	global_load_dwordx4 v[180:183], v[132:133], off
	global_load_dwordx4 v[146:149], v[132:133], off offset:256
	v_add_co_u32_e32 v132, vcc, s31, v130
	s_waitcnt vmcnt(0) lgkmcnt(0)
	v_lshlrev_b32_e32 v186, 16, v172
	v_addc_co_u32_e32 v133, vcc, 0, v131, vcc
	global_load_dwordx4 v[142:145], v[132:133], off
	global_load_dwordx4 v[138:141], v[132:133], off offset:256
	v_add_co_u32_e32 v130, vcc, s46, v130
	v_and_b32_e32 v187, 0xffff0000, v172
	s_nop 0
	v_addc_co_u32_e32 v131, vcc, 0, v131, vcc
	global_load_dwordx4 v[134:137], v[130:131], off
	s_nop 0
	global_load_dwordx4 v[130:133], v[130:131], off offset:256
	v_lshlrev_b32_e32 v172, 16, v173
	v_and_b32_e32 v173, 0xffff0000, v173
	v_lshlrev_b32_e32 v188, 16, v174
	v_and_b32_e32 v189, 0xffff0000, v174
	v_lshlrev_b32_e32 v174, 16, v175
	v_and_b32_e32 v175, 0xffff0000, v175
	v_pk_fma_f32 v[128:129], v[172:173], s[30:31], v[128:129] op_sel_hi:[1,0,1]
	v_pk_fma_f32 v[126:127], v[186:187], s[30:31], v[126:127] op_sel_hi:[1,0,1]
	v_pk_fma_f32 v[172:173], v[174:175], s[30:31], v[124:125] op_sel_hi:[1,0,1]
	v_pk_fma_f32 v[122:123], v[188:189], s[30:31], v[122:123] op_sel_hi:[1,0,1]
	v_cvt_pk_bf16_f32 v124, v126, v127
	v_cvt_pk_bf16_f32 v125, v128, v129
	v_cvt_pk_bf16_f32 v126, v122, v123
	v_cvt_pk_bf16_f32 v127, v172, v173
	v_lshl_add_u64 v[122:123], s[20:21], 0, v[184:185]
	global_store_dwordx4 v[122:123], v[124:127], off
	v_lshlrev_b32_e32 v128, 16, v178
	v_and_b32_e32 v129, 0xffff0000, v178
	v_lshlrev_b32_e32 v124, 16, v176
	v_and_b32_e32 v125, 0xffff0000, v176
	v_lshlrev_b32_e32 v126, 16, v177
	v_and_b32_e32 v127, 0xffff0000, v177
	v_lshlrev_b32_e32 v172, 16, v179
	v_and_b32_e32 v173, 0xffff0000, v179
	v_pk_fma_f32 v[116:117], v[126:127], s[30:31], v[116:117] op_sel_hi:[1,0,1]
	v_pk_fma_f32 v[114:115], v[124:125], s[30:31], v[114:115] op_sel_hi:[1,0,1]
	v_pk_fma_f32 v[124:125], v[172:173], s[30:31], v[108:109] op_sel_hi:[1,0,1]
	v_pk_fma_f32 v[108:109], v[128:129], s[30:31], v[106:107] op_sel_hi:[1,0,1]
	v_cvt_pk_bf16_f32 v106, v114, v115
	v_cvt_pk_bf16_f32 v107, v116, v117
	v_cvt_pk_bf16_f32 v108, v108, v109
	v_cvt_pk_bf16_f32 v109, v124, v125
	global_store_dwordx4 v[122:123], v[106:109], off offset:256
	v_lshlrev_b32_e32 v114, 16, v182
	v_and_b32_e32 v115, 0xffff0000, v182
	v_lshlrev_b32_e32 v106, 16, v180
	v_and_b32_e32 v107, 0xffff0000, v180
	v_lshlrev_b32_e32 v108, 16, v181
	v_and_b32_e32 v109, 0xffff0000, v181
	v_lshlrev_b32_e32 v116, 16, v183
	v_and_b32_e32 v117, 0xffff0000, v183
	v_pk_fma_f32 v[108:109], v[108:109], s[30:31], v[120:121] op_sel_hi:[1,0,1]
	v_pk_fma_f32 v[106:107], v[106:107], s[30:31], v[118:119] op_sel_hi:[1,0,1]
	v_pk_fma_f32 v[110:111], v[114:115], s[30:31], v[110:111] op_sel_hi:[1,0,1]
	v_pk_fma_f32 v[112:113], v[116:117], s[30:31], v[112:113] op_sel_hi:[1,0,1]
	v_cvt_pk_bf16_f32 v106, v106, v107
	v_cvt_pk_bf16_f32 v107, v108, v109
	v_cvt_pk_bf16_f32 v108, v110, v111
	v_add_co_u32_e32 v110, vcc, s47, v122
	v_cvt_pk_bf16_f32 v109, v112, v113
	s_nop 0
	v_addc_co_u32_e32 v111, vcc, 0, v123, vcc
	global_store_dwordx4 v[110:111], v[106:109], off
	v_lshlrev_b32_e32 v112, 16, v148
	v_and_b32_e32 v113, 0xffff0000, v148
	v_lshlrev_b32_e32 v106, 16, v146
	v_and_b32_e32 v107, 0xffff0000, v146
	v_lshlrev_b32_e32 v108, 16, v147
	v_and_b32_e32 v109, 0xffff0000, v147
	v_lshlrev_b32_e32 v114, 16, v149
	v_and_b32_e32 v115, 0xffff0000, v149
	v_pk_fma_f32 v[104:105], v[108:109], s[30:31], v[104:105] op_sel_hi:[1,0,1]
	v_pk_fma_f32 v[102:103], v[106:107], s[30:31], v[102:103] op_sel_hi:[1,0,1]
	v_pk_fma_f32 v[106:107], v[114:115], s[30:31], v[96:97] op_sel_hi:[1,0,1]
	v_pk_fma_f32 v[96:97], v[112:113], s[30:31], v[94:95] op_sel_hi:[1,0,1]
	v_cvt_pk_bf16_f32 v94, v102, v103
	v_cvt_pk_bf16_f32 v95, v104, v105
	v_cvt_pk_bf16_f32 v96, v96, v97
	v_cvt_pk_bf16_f32 v97, v106, v107
	global_store_dwordx4 v[110:111], v[94:97], off offset:256
	s_waitcnt vmcnt(0) lgkmcnt(0)
	v_lshlrev_b32_e32 v102, 16, v144
	v_lshlrev_b32_e32 v94, 16, v142
	v_and_b32_e32 v95, 0xffff0000, v142
	v_lshlrev_b32_e32 v96, 16, v143
	v_and_b32_e32 v97, 0xffff0000, v143
	v_and_b32_e32 v103, 0xffff0000, v144
	v_lshlrev_b32_e32 v104, 16, v145
	v_and_b32_e32 v105, 0xffff0000, v145
	v_pk_fma_f32 v[94:95], v[94:95], s[30:31], v[98:99] op_sel_hi:[1,0,1]
	v_pk_fma_f32 v[96:97], v[96:97], s[30:31], v[100:101] op_sel_hi:[1,0,1]
	v_pk_fma_f32 v[98:99], v[104:105], s[30:31], v[92:93] op_sel_hi:[1,0,1]
	v_pk_fma_f32 v[92:93], v[102:103], s[30:31], v[90:91] op_sel_hi:[1,0,1]
	v_cvt_pk_bf16_f32 v90, v94, v95
	v_add_co_u32_e32 v94, vcc, s31, v122
	v_cvt_pk_bf16_f32 v91, v96, v97
	v_cvt_pk_bf16_f32 v92, v92, v93
	v_cvt_pk_bf16_f32 v93, v98, v99
	v_addc_co_u32_e32 v95, vcc, 0, v123, vcc
	global_store_dwordx4 v[94:95], v[90:93], off
	v_lshlrev_b32_e32 v96, 16, v140
	v_and_b32_e32 v97, 0xffff0000, v140
	v_lshlrev_b32_e32 v90, 16, v138
	v_and_b32_e32 v91, 0xffff0000, v138
	v_lshlrev_b32_e32 v92, 16, v139
	v_and_b32_e32 v93, 0xffff0000, v139
	v_lshlrev_b32_e32 v98, 16, v141
	v_and_b32_e32 v99, 0xffff0000, v141
	v_pk_fma_f32 v[88:89], v[92:93], s[30:31], v[88:89] op_sel_hi:[1,0,1]
	v_pk_fma_f32 v[86:87], v[90:91], s[30:31], v[86:87] op_sel_hi:[1,0,1]
	v_pk_fma_f32 v[90:91], v[98:99], s[30:31], v[80:81] op_sel_hi:[1,0,1]
	v_pk_fma_f32 v[80:81], v[96:97], s[30:31], v[78:79] op_sel_hi:[1,0,1]
	v_cvt_pk_bf16_f32 v78, v86, v87
	v_cvt_pk_bf16_f32 v79, v88, v89
	v_cvt_pk_bf16_f32 v80, v80, v81
	v_cvt_pk_bf16_f32 v81, v90, v91
	global_store_dwordx4 v[94:95], v[78:81], off offset:256
	v_lshlrev_b32_e32 v86, 16, v136
	v_and_b32_e32 v87, 0xffff0000, v136
	v_lshlrev_b32_e32 v78, 16, v134
	v_and_b32_e32 v79, 0xffff0000, v134
	v_lshlrev_b32_e32 v80, 16, v135
	v_and_b32_e32 v81, 0xffff0000, v135
	v_lshlrev_b32_e32 v88, 16, v137
	v_and_b32_e32 v89, 0xffff0000, v137
	v_pk_fma_f32 v[78:79], v[78:79], s[30:31], v[82:83] op_sel_hi:[1,0,1]
	v_pk_fma_f32 v[80:81], v[80:81], s[30:31], v[84:85] op_sel_hi:[1,0,1]
	v_pk_fma_f32 v[82:83], v[88:89], s[30:31], v[76:77] op_sel_hi:[1,0,1]
	v_pk_fma_f32 v[76:77], v[86:87], s[30:31], v[74:75] op_sel_hi:[1,0,1]
	v_cvt_pk_bf16_f32 v74, v78, v79
	v_add_co_u32_e32 v78, vcc, s46, v122
	v_cvt_pk_bf16_f32 v75, v80, v81
	v_cvt_pk_bf16_f32 v76, v76, v77
	v_cvt_pk_bf16_f32 v77, v82, v83
	v_addc_co_u32_e32 v79, vcc, 0, v123, vcc
	global_store_dwordx4 v[78:79], v[74:77], off
	v_lshlrev_b32_e32 v80, 16, v132
	v_and_b32_e32 v81, 0xffff0000, v132
	v_lshlrev_b32_e32 v74, 16, v130
	v_and_b32_e32 v75, 0xffff0000, v130
	v_lshlrev_b32_e32 v76, 16, v131
	v_and_b32_e32 v77, 0xffff0000, v131
	v_lshlrev_b32_e32 v82, 16, v133
	v_and_b32_e32 v83, 0xffff0000, v133
	v_pk_fma_f32 v[72:73], v[76:77], s[30:31], v[72:73] op_sel_hi:[1,0,1]
	v_pk_fma_f32 v[70:71], v[74:75], s[30:31], v[70:71] op_sel_hi:[1,0,1]
	v_pk_fma_f32 v[74:75], v[82:83], s[30:31], v[68:69] op_sel_hi:[1,0,1]
	v_pk_fma_f32 v[68:69], v[80:81], s[30:31], v[66:67] op_sel_hi:[1,0,1]
	v_cvt_pk_bf16_f32 v66, v70, v71
	v_cvt_pk_bf16_f32 v67, v72, v73
	v_cvt_pk_bf16_f32 v68, v68, v69
	v_cvt_pk_bf16_f32 v69, v74, v75
	global_store_dwordx4 v[78:79], v[66:69], off offset:256
	s_nop 1
	v_add_u32_e32 v66, 0x80, v171
	s_nop 0
	v_ashrrev_i32_e32 v67, 31, v66
	v_lshlrev_b64 v[66:67], 10, v[66:67]
	v_lshl_add_u64 v[66:67], v[66:67], 0, v[164:165]
	v_lshlrev_b64 v[98:99], 1, v[66:67]
	v_lshl_add_u64 v[90:91], s[14:15], 0, v[98:99]
	global_load_dwordx4 v[66:69], v[90:91], off
	global_load_dwordx4 v[70:73], v[90:91], off offset:256
	v_add_co_u32_e32 v78, vcc, s47, v90
	s_waitcnt vmcnt(0) lgkmcnt(0)
	v_lshlrev_b32_e32 v100, 16, v66
	v_addc_co_u32_e32 v79, vcc, 0, v91, vcc
	global_load_dwordx4 v[74:77], v[78:79], off
	s_nop 0
	global_load_dwordx4 v[78:81], v[78:79], off offset:256
	v_add_co_u32_e32 v86, vcc, s31, v90
	v_and_b32_e32 v101, 0xffff0000, v66
	s_nop 0
	v_addc_co_u32_e32 v87, vcc, 0, v91, vcc
	global_load_dwordx4 v[82:85], v[86:87], off
	s_nop 0
	global_load_dwordx4 v[86:89], v[86:87], off offset:256
	v_add_co_u32_e32 v94, vcc, s46, v90
	v_lshlrev_b32_e32 v66, 16, v67
	s_nop 0
	v_addc_co_u32_e32 v95, vcc, 0, v91, vcc
	global_load_dwordx4 v[90:93], v[94:95], off
	s_nop 0
	global_load_dwordx4 v[94:97], v[94:95], off offset:256
	v_and_b32_e32 v67, 0xffff0000, v67
	v_lshlrev_b32_e32 v102, 16, v68
	v_and_b32_e32 v103, 0xffff0000, v68
	v_lshlrev_b32_e32 v68, 16, v69
	v_and_b32_e32 v69, 0xffff0000, v69
	v_pk_fma_f32 v[64:65], v[66:67], s[30:31], v[64:65] op_sel_hi:[1,0,1]
	v_pk_fma_f32 v[62:63], v[100:101], s[30:31], v[62:63] op_sel_hi:[1,0,1]
	v_pk_fma_f32 v[66:67], v[68:69], s[30:31], v[60:61] op_sel_hi:[1,0,1]
	v_pk_fma_f32 v[60:61], v[102:103], s[30:31], v[58:59] op_sel_hi:[1,0,1]
	v_cvt_pk_bf16_f32 v58, v62, v63
	v_cvt_pk_bf16_f32 v59, v64, v65
	v_cvt_pk_bf16_f32 v60, v60, v61
	v_cvt_pk_bf16_f32 v61, v66, v67
	v_lshl_add_u64 v[62:63], s[20:21], 0, v[98:99]
	global_store_dwordx4 v[62:63], v[58:61], off
	v_lshlrev_b32_e32 v64, 16, v72
	v_and_b32_e32 v65, 0xffff0000, v72
	v_lshlrev_b32_e32 v58, 16, v70
	v_and_b32_e32 v59, 0xffff0000, v70
	v_lshlrev_b32_e32 v60, 16, v71
	v_and_b32_e32 v61, 0xffff0000, v71
	v_lshlrev_b32_e32 v66, 16, v73
	v_and_b32_e32 v67, 0xffff0000, v73
	v_pk_fma_f32 v[56:57], v[60:61], s[30:31], v[56:57] op_sel_hi:[1,0,1]
	v_pk_fma_f32 v[54:55], v[58:59], s[30:31], v[54:55] op_sel_hi:[1,0,1]
	v_pk_fma_f32 v[58:59], v[66:67], s[30:31], v[48:49] op_sel_hi:[1,0,1]
	v_pk_fma_f32 v[48:49], v[64:65], s[30:31], v[46:47] op_sel_hi:[1,0,1]
	v_cvt_pk_bf16_f32 v46, v54, v55
	v_cvt_pk_bf16_f32 v47, v56, v57
	v_cvt_pk_bf16_f32 v48, v48, v49
	v_cvt_pk_bf16_f32 v49, v58, v59
	global_store_dwordx4 v[62:63], v[46:49], off offset:256
	s_waitcnt vmcnt(0) lgkmcnt(0)
	v_lshlrev_b32_e32 v54, 16, v76
	v_lshlrev_b32_e32 v46, 16, v74
	v_and_b32_e32 v47, 0xffff0000, v74
	v_lshlrev_b32_e32 v48, 16, v75
	v_and_b32_e32 v49, 0xffff0000, v75
	v_and_b32_e32 v55, 0xffff0000, v76
	v_lshlrev_b32_e32 v56, 16, v77
	v_and_b32_e32 v57, 0xffff0000, v77
	v_pk_fma_f32 v[46:47], v[46:47], s[30:31], v[50:51] op_sel_hi:[1,0,1]
	v_pk_fma_f32 v[48:49], v[48:49], s[30:31], v[52:53] op_sel_hi:[1,0,1]
	v_pk_fma_f32 v[50:51], v[56:57], s[30:31], v[44:45] op_sel_hi:[1,0,1]
	v_pk_fma_f32 v[44:45], v[54:55], s[30:31], v[42:43] op_sel_hi:[1,0,1]
	v_cvt_pk_bf16_f32 v42, v46, v47
	v_add_co_u32_e32 v46, vcc, s47, v62
	v_cvt_pk_bf16_f32 v43, v48, v49
	v_cvt_pk_bf16_f32 v44, v44, v45
	v_cvt_pk_bf16_f32 v45, v50, v51
	v_addc_co_u32_e32 v47, vcc, 0, v63, vcc
	global_store_dwordx4 v[46:47], v[42:45], off
	v_lshlrev_b32_e32 v48, 16, v80
	v_and_b32_e32 v49, 0xffff0000, v80
	v_lshlrev_b32_e32 v42, 16, v78
	v_and_b32_e32 v43, 0xffff0000, v78
	v_lshlrev_b32_e32 v44, 16, v79
	v_and_b32_e32 v45, 0xffff0000, v79
	v_lshlrev_b32_e32 v50, 16, v81
	v_and_b32_e32 v51, 0xffff0000, v81
	v_pk_fma_f32 v[40:41], v[44:45], s[30:31], v[40:41] op_sel_hi:[1,0,1]
	v_pk_fma_f32 v[38:39], v[42:43], s[30:31], v[38:39] op_sel_hi:[1,0,1]
	v_pk_fma_f32 v[42:43], v[50:51], s[30:31], v[32:33] op_sel_hi:[1,0,1]
	v_pk_fma_f32 v[32:33], v[48:49], s[30:31], v[30:31] op_sel_hi:[1,0,1]
	v_cvt_pk_bf16_f32 v30, v38, v39
	v_cvt_pk_bf16_f32 v31, v40, v41
	v_cvt_pk_bf16_f32 v32, v32, v33
	v_cvt_pk_bf16_f32 v33, v42, v43
	global_store_dwordx4 v[46:47], v[30:33], off offset:256
	v_lshlrev_b32_e32 v38, 16, v84
	v_and_b32_e32 v39, 0xffff0000, v84
	v_lshlrev_b32_e32 v30, 16, v82
	v_and_b32_e32 v31, 0xffff0000, v82
	v_lshlrev_b32_e32 v32, 16, v83
	v_and_b32_e32 v33, 0xffff0000, v83
	v_lshlrev_b32_e32 v40, 16, v85
	v_and_b32_e32 v41, 0xffff0000, v85
	v_pk_fma_f32 v[30:31], v[30:31], s[30:31], v[34:35] op_sel_hi:[1,0,1]
	v_pk_fma_f32 v[32:33], v[32:33], s[30:31], v[36:37] op_sel_hi:[1,0,1]
	v_pk_fma_f32 v[34:35], v[40:41], s[30:31], v[28:29] op_sel_hi:[1,0,1]
	v_pk_fma_f32 v[28:29], v[38:39], s[30:31], v[26:27] op_sel_hi:[1,0,1]
	v_cvt_pk_bf16_f32 v26, v30, v31
	v_add_co_u32_e32 v30, vcc, s31, v62
	v_cvt_pk_bf16_f32 v27, v32, v33
	v_cvt_pk_bf16_f32 v28, v28, v29
	v_cvt_pk_bf16_f32 v29, v34, v35
	v_addc_co_u32_e32 v31, vcc, 0, v63, vcc
	global_store_dwordx4 v[30:31], v[26:29], off
	v_lshlrev_b32_e32 v32, 16, v88
	v_and_b32_e32 v33, 0xffff0000, v88
	v_lshlrev_b32_e32 v26, 16, v86
	v_and_b32_e32 v27, 0xffff0000, v86
	v_lshlrev_b32_e32 v28, 16, v87
	v_and_b32_e32 v29, 0xffff0000, v87
	v_lshlrev_b32_e32 v34, 16, v89
	v_and_b32_e32 v35, 0xffff0000, v89
	v_pk_fma_f32 v[24:25], v[28:29], s[30:31], v[24:25] op_sel_hi:[1,0,1]
	v_pk_fma_f32 v[22:23], v[26:27], s[30:31], v[22:23] op_sel_hi:[1,0,1]
	v_pk_fma_f32 v[26:27], v[34:35], s[30:31], v[16:17] op_sel_hi:[1,0,1]
	v_pk_fma_f32 v[16:17], v[32:33], s[30:31], v[14:15] op_sel_hi:[1,0,1]
	v_cvt_pk_bf16_f32 v14, v22, v23
	v_cvt_pk_bf16_f32 v15, v24, v25
	v_cvt_pk_bf16_f32 v16, v16, v17
	v_cvt_pk_bf16_f32 v17, v26, v27
	global_store_dwordx4 v[30:31], v[14:17], off offset:256
	v_lshlrev_b32_e32 v22, 16, v92
	v_and_b32_e32 v23, 0xffff0000, v92
	v_lshlrev_b32_e32 v14, 16, v90
	v_and_b32_e32 v15, 0xffff0000, v90
	v_lshlrev_b32_e32 v16, 16, v91
	v_and_b32_e32 v17, 0xffff0000, v91
	v_lshlrev_b32_e32 v24, 16, v93
	v_and_b32_e32 v25, 0xffff0000, v93
	v_pk_fma_f32 v[14:15], v[14:15], s[30:31], v[18:19] op_sel_hi:[1,0,1]
	v_pk_fma_f32 v[16:17], v[16:17], s[30:31], v[20:21] op_sel_hi:[1,0,1]
	v_pk_fma_f32 v[18:19], v[24:25], s[30:31], v[12:13] op_sel_hi:[1,0,1]
	v_pk_fma_f32 v[12:13], v[22:23], s[30:31], v[10:11] op_sel_hi:[1,0,1]
	v_cvt_pk_bf16_f32 v10, v14, v15
	v_add_co_u32_e32 v14, vcc, s46, v62
	v_cvt_pk_bf16_f32 v11, v16, v17
	v_cvt_pk_bf16_f32 v12, v12, v13
	v_cvt_pk_bf16_f32 v13, v18, v19
	v_addc_co_u32_e32 v15, vcc, 0, v63, vcc
	global_store_dwordx4 v[14:15], v[10:13], off
	v_lshlrev_b32_e32 v16, 16, v96
	v_and_b32_e32 v17, 0xffff0000, v96
	v_lshlrev_b32_e32 v10, 16, v94
	v_and_b32_e32 v11, 0xffff0000, v94
	v_lshlrev_b32_e32 v12, 16, v95
	v_and_b32_e32 v13, 0xffff0000, v95
	v_lshlrev_b32_e32 v18, 16, v97
	v_and_b32_e32 v19, 0xffff0000, v97
	v_pk_fma_f32 v[8:9], v[12:13], s[30:31], v[8:9] op_sel_hi:[1,0,1]
	v_pk_fma_f32 v[6:7], v[10:11], s[30:31], v[6:7] op_sel_hi:[1,0,1]
	v_pk_fma_f32 v[10:11], v[18:19], s[30:31], v[4:5] op_sel_hi:[1,0,1]
	v_pk_fma_f32 v[4:5], v[16:17], s[30:31], v[2:3] op_sel_hi:[1,0,1]
	v_cvt_pk_bf16_f32 v2, v6, v7
	v_cvt_pk_bf16_f32 v3, v8, v9
	v_cvt_pk_bf16_f32 v4, v4, v5
	v_cvt_pk_bf16_f32 v5, v10, v11
	s_and_b64 vcc, exec, s[34:35]
	global_store_dwordx4 v[14:15], v[2:5], off offset:256
	s_cbranch_vccz .LBB0_1785
	s_waitcnt vmcnt(0)
	s_cmpk_gt_u32 s4, 0xff
	s_cbranch_scc1 .LBB0_1790
	s_barrier

.LBB0_1807:
	s_or_b64 exec, exec, s[22:23]
	s_lshl_b32 s0, s7, 8
	s_add_i32 s0, s0, s97
	s_ashr_i32 s1, s0, 31
	s_lshl_b64 s[8:9], s[0:1], 11
	v_lshl_add_u64 v[38:39], v[54:55], 0, s[8:9]
	v_add_co_u32_e32 v44, vcc, 0x4000, v38
	s_waitcnt lgkmcnt(0)
	s_barrier
	global_load_dwordx4 v[2:5], v[50:51], off
	global_load_dwordx4 v[6:9], v[50:51], off offset:1024
	global_load_dwordx4 v[10:13], v[52:53], off
	global_load_dwordx4 v[14:17], v[52:53], off offset:1024
	global_load_dwordx4 v[18:21], v[50:51], off offset:2048
	global_load_dwordx4 v[22:25], v[50:51], off offset:3072
	global_load_dwordx4 v[26:29], v[52:53], off offset:2048
	global_load_dwordx4 v[30:33], v[52:53], off offset:3072
	v_lshl_add_u64 v[42:43], v[38:39], 0, s[28:29]
	v_addc_co_u32_e32 v45, vcc, 0, v39, vcc
	global_load_dwordx2 v[36:37], v[38:39], off
	global_load_dwordx2 v[34:35], v[38:39], off offset:512
	global_load_dwordx2 v[40:41], v[38:39], off offset:1024
	s_nop 0
	global_load_dwordx2 v[38:39], v[38:39], off offset:1536
	s_nop 0
	global_load_dwordx2 v[60:61], v[44:45], off
	global_load_dwordx2 v[62:63], v[42:43], off offset:512
	global_load_dwordx2 v[64:65], v[42:43], off offset:1024
	global_load_dwordx2 v[66:67], v[42:43], off offset:1536
	s_mov_b32 s8, 0
	s_add_i32 s9, s0, 16
	s_mov_b32 s10, 0
	s_branch .LBB0_1810

.LBB0_1810:
	s_waitcnt vmcnt(0) lgkmcnt(0)
	v_lshlrev_b32_e32 v77, 16, v37
	v_lshlrev_b32_e32 v76, 16, v36
	v_and_b32_e32 v37, 0xffff0000, v37
	v_and_b32_e32 v36, 0xffff0000, v36
	v_pk_add_f32 v[68:69], v[76:77], v[36:37]
	v_lshlrev_b32_e32 v87, 16, v35
	v_lshlrev_b32_e32 v86, 16, v34
	v_and_b32_e32 v35, 0xffff0000, v35
	v_and_b32_e32 v34, 0xffff0000, v34
	v_lshlrev_b32_e32 v46, 16, v39
	v_and_b32_e32 v48, 0xffff0000, v39
	v_add_f32_e32 v39, v68, v69
	v_pk_add_f32 v[68:69], v[86:87], v[34:35]
	v_lshlrev_b32_e32 v42, 16, v40
	v_and_b32_e32 v43, 0xffff0000, v40
	v_lshlrev_b32_e32 v40, 16, v41
	v_and_b32_e32 v41, 0xffff0000, v41
	v_pk_add_f32 v[68:69], v[68:69], v[68:69] op_sel_hi:[0,1]
	v_lshlrev_b32_e32 v44, 16, v38
	v_and_b32_e32 v38, 0xffff0000, v38
	v_add_f32_e32 v49, 0, v39
	v_add_f32_e32 v45, v42, v43
	v_add_f32_e32 v39, v40, v41
	v_mov_b32_e32 v47, v69
	v_pk_add_f32 v[70:71], v[44:45], v[38:39]
	v_pk_add_f32 v[68:69], v[46:47], v[48:49]
	s_min_u32 s0, s10, 29
	v_pk_add_f32 v[68:69], v[70:71], v[68:69]
	s_lshl_b32 s0, s0, 3
	v_add_f32_e32 v39, v68, v69
	s_add_i32 s22, s9, s0
	s_nop 0
	v_add_f32_dpp v39, v39, v39 quad_perm:[1,0,3,2] row_mask:0xf bank_mask:0xf bound_ctrl:1
	s_nop 1
	v_add_f32_dpp v39, v39, v39 quad_perm:[2,3,0,1] row_mask:0xf bank_mask:0xf bound_ctrl:1
	s_nop 1
	v_add_f32_dpp v39, v39, v39 row_half_mirror row_mask:0xf bank_mask:0xf bound_ctrl:1
	s_nop 1
	v_add_f32_dpp v39, v39, v39 row_mirror row_mask:0xf bank_mask:0xf bound_ctrl:1
	s_nop 0
	v_readlane_b32 s11, v39, 16
	v_readlane_b32 s23, v39, 48
	v_readlane_b32 s0, v39, 0
	v_readlane_b32 s1, v39, 32
	v_mov_b32_e32 v68, s11
	v_mov_b32_e32 v69, s23
	v_pk_add_f32 v[68:69], s[0:1], v[68:69]
	s_nop 0
	v_add_f32_e32 v39, v68, v69
	v_fmac_f32_e32 v36, 0xba800000, v39
	v_fmac_f32_e32 v37, 0xba800000, v39
	v_fmac_f32_e32 v77, 0xba800000, v39
	v_fmac_f32_e32 v76, 0xba800000, v39
	v_mov_b32_e32 v88, v77
	v_mov_b32_e32 v89, v37
	v_mov_b32_e32 v77, v36
	v_fmac_f32_e32 v34, 0xba800000, v39
	v_fmac_f32_e32 v35, 0xba800000, v39
	v_fmac_f32_e32 v87, 0xba800000, v39
	v_pk_mul_f32 v[68:69], v[88:89], v[88:89]
	v_pk_mul_f32 v[36:37], v[76:77], v[76:77]
	v_fmac_f32_e32 v86, 0xba800000, v39
	v_mov_b32_e32 v90, v87
	v_mov_b32_e32 v91, v35
	v_mov_b32_e32 v87, v34
	v_pk_mov_b32 v[70:71], v[36:37], v[68:69] op_sel:[1,0]
	v_mov_b32_e32 v37, v69
	v_pk_mul_f32 v[68:69], v[90:91], v[90:91]
	v_pk_mul_f32 v[34:35], v[86:87], v[86:87]
	v_pk_add_f32 v[36:37], v[70:71], v[36:37]
	v_pk_mov_b32 v[70:71], v[34:35], v[68:69] op_sel:[1,0]
	v_mov_b32_e32 v35, v69
	v_pk_add_f32 v[34:35], v[70:71], v[34:35]
	v_fmac_f32_e32 v42, 0xba800000, v39
	v_pk_add_f32 v[34:35], v[34:35], v[34:35] op_sel_hi:[0,1]
	v_fmac_f32_e32 v43, 0xba800000, v39
	v_fmac_f32_e32 v40, 0xba800000, v39
	v_mul_f32_e32 v34, v42, v42
	v_fmac_f32_e32 v41, 0xba800000, v39
	v_pk_fma_f32 v[68:69], v[42:43], v[42:43], v[34:35] op_sel_hi:[1,1,0]
	v_mul_f32_e32 v34, v40, v40
	v_pk_add_f32 v[36:37], v[36:37], v[36:37] op_sel_hi:[0,1]
	v_pk_fma_f32 v[70:71], v[40:41], v[40:41], v[34:35] op_sel_hi:[1,1,0]
	v_fmac_f32_e32 v48, 0xba800000, v39
	v_fmac_f32_e32 v46, 0xba800000, v39
	v_fmac_f32_e32 v38, 0xba800000, v39
	v_fmac_f32_e32 v44, 0xba800000, v39
	v_mul_f32_e32 v68, v44, v44
	v_mul_f32_e32 v70, v38, v38
	v_mul_f32_e32 v36, v46, v46
	v_mul_f32_e32 v34, v48, v48
	v_pk_add_f32 v[68:69], v[68:69], v[70:71]
	v_pk_add_f32 v[34:35], v[36:37], v[34:35]
	v_mov_b32_e32 v47, v48
	v_pk_add_f32 v[34:35], v[68:69], v[34:35]
	s_nop 0
	v_add_f32_e32 v34, v34, v35
	s_nop 1
	v_add_f32_dpp v34, v34, v34 quad_perm:[1,0,3,2] row_mask:0xf bank_mask:0xf bound_ctrl:1
	s_nop 1
	v_add_f32_dpp v34, v34, v34 quad_perm:[2,3,0,1] row_mask:0xf bank_mask:0xf bound_ctrl:1
	s_nop 1
	v_add_f32_dpp v34, v34, v34 row_half_mirror row_mask:0xf bank_mask:0xf bound_ctrl:1
	s_nop 1
	v_add_f32_dpp v34, v34, v34 row_mirror row_mask:0xf bank_mask:0xf bound_ctrl:1
	s_nop 0
	v_readlane_b32 s11, v34, 16
	v_readlane_b32 s23, v34, 48
	v_readlane_b32 s0, v34, 0
	v_readlane_b32 s1, v34, 32
	v_mov_b32_e32 v34, s11
	v_mov_b32_e32 v35, s23
	v_pk_add_f32 v[34:35], s[0:1], v[34:35]
	s_mov_b32 s0, 0xf800000
	v_add_f32_e32 v34, v34, v35
	v_fmamk_f32 v34, v34, 0x3a800000, v83
	s_ashr_i32 s23, s22, 31
	v_mul_f32_e32 v35, 0x4f800000, v34
	v_cmp_gt_f32_e32 vcc, s0, v34
	s_lshl_b64 s[0:1], s[22:23], 11
	s_and_b32 s11, s10, 3
	v_cndmask_b32_e32 v36, v34, v35, vcc
	v_lshl_add_u64 v[34:35], v[54:55], 0, s[0:1]
	global_load_dwordx2 v[68:69], v[34:35], off
	global_load_dwordx2 v[70:71], v[34:35], off offset:512
	global_load_dwordx2 v[72:73], v[34:35], off offset:1024
	global_load_dwordx2 v[74:75], v[34:35], off offset:1536
	v_sqrt_f32_e32 v37, v36
	s_mul_i32 s26, s11, 0x810
	s_add_i32 s26, s87, s26
	v_add_u32_e32 v39, -1, v37
	v_fma_f32 v45, -v39, v37, v36
	v_cmp_ge_f32_e64 s[22:23], 0, v45
	v_add_u32_e32 v45, 1, v37
	s_nop 0
	v_cndmask_b32_e64 v39, v37, v39, s[22:23]
	v_fma_f32 v37, -v45, v37, v36
	v_cmp_lt_f32_e64 s[22:23], 0, v37
	s_nop 1
	v_cndmask_b32_e64 v37, v39, v45, s[22:23]
	v_mul_f32_e32 v39, 0x37800000, v37
	v_cndmask_b32_e32 v37, v37, v39, vcc
	v_cmp_class_f32_e32 vcc, v36, v84
	s_add_i32 s22, s4, s8
	s_ashr_i32 s23, s22, 31
	v_cndmask_b32_e32 v36, v37, v36, vcc
	v_div_scale_f32 v37, s[0:1], v36, v36, 1.0
	v_rcp_f32_e32 v39, v37
	s_lshl_b64 s[0:1], s[22:23], 11
	v_fma_f32 v34, -v37, v39, 1.0
	v_fmac_f32_e32 v39, v34, v39
	v_div_scale_f32 v34, vcc, 1.0, v36, 1.0
	v_mul_f32_e32 v35, v34, v39
	v_fma_f32 v45, -v37, v35, v34
	v_fmac_f32_e32 v35, v45, v39
	v_fma_f32 v34, -v37, v35, v34
	v_div_fmas_f32 v34, v34, v39, v35
	v_div_fixup_f32 v34, v34, v36, 1.0
	v_mov_b32_e32 v45, v38
	v_pk_mul_f32 v[36:37], v[76:77], v[34:35] op_sel_hi:[1,0]
	v_pk_mul_f32 v[76:77], v[88:89], v[34:35] op_sel_hi:[1,0]
	v_pk_mul_f32 v[38:39], v[44:45], v[34:35] op_sel_hi:[1,0]
	v_mov_b32_e32 v44, v78
	v_pk_fma_f32 v[76:77], v[4:5], v[76:77], v[12:13]
	v_pk_fma_f32 v[36:37], v[2:3], v[36:37], v[10:11]
	v_pk_mul_f32 v[86:87], v[86:87], v[34:35] op_sel_hi:[1,0]
	v_pk_mul_f32 v[88:89], v[90:91], v[34:35] op_sel_hi:[1,0]
	v_pk_fma_f32 v[86:87], v[6:7], v[86:87], v[14:15]
	v_pk_fma_f32 v[88:89], v[8:9], v[88:89], v[16:17]
	v_pk_mul_f32 v[42:43], v[42:43], v[34:35] op_sel_hi:[1,0]
	v_pk_mul_f32 v[40:41], v[40:41], v[34:35] op_sel_hi:[1,0]
	v_pk_mul_f32 v[34:35], v[46:47], v[34:35] op_sel_hi:[1,0]
	v_lshl_add_u32 v48, v44, 3, s26
	v_cvt_pk_bf16_f32 v44, v36, v37
	v_cvt_pk_bf16_f32 v45, v76, v77
	v_lshl_add_u64 v[46:47], v[56:57], 0, s[0:1]
	v_pk_fma_f32 v[40:41], v[20:21], v[40:41], v[28:29]
	v_pk_fma_f32 v[42:43], v[18:19], v[42:43], v[26:27]
	global_store_dwordx2 v[46:47], v[44:45], off
	ds_write_b64 v48, v[44:45] offset:33024
	v_cvt_pk_bf16_f32 v44, v86, v87
	v_cvt_pk_bf16_f32 v45, v88, v89
	v_pk_fma_f32 v[34:35], v[24:25], v[34:35], v[32:33]
	v_pk_fma_f32 v[38:39], v[22:23], v[38:39], v[30:31]
	global_store_dwordx2 v[46:47], v[44:45], off offset:512
	ds_write_b64 v48, v[44:45] offset:33536
	v_cvt_pk_bf16_f32 v44, v42, v43
	v_cvt_pk_bf16_f32 v45, v40, v41
	global_store_dwordx2 v[46:47], v[44:45], off offset:1024
	ds_write_b64 v48, v[44:45] offset:34048
	v_cvt_pk_bf16_f32 v44, v38, v39
	v_cvt_pk_bf16_f32 v45, v34, v35
	global_store_dwordx2 v[46:47], v[44:45], off offset:1536
	ds_write_b64 v48, v[44:45] offset:34560
	v_med3_f32 v36, v36, s6, v85
	v_med3_f32 v37, v37, s6, v85
	v_mov_b32_e32 v44, 0
	v_cvt_pk_fp8_f32 v44, v36, v37
	v_med3_f32 v36, v76, s6, v85
	v_med3_f32 v37, v77, s6, v85
	v_med3_f32 v45, v86, s6, v85
	v_cvt_pk_fp8_f32 v44, v36, v37 op_sel:[0,0,1]
	v_med3_f32 v46, v87, s6, v85
	v_mov_b32_e32 v47, 0
	v_cvt_pk_fp8_f32 v47, v45, v46
	s_lshl_b64 s[0:1], s[22:23], 10
	v_lshl_add_u64 v[36:37], v[58:59], 0, s[0:1]
	global_store_dword v[36:37], v44, off
	v_med3_f32 v44, v88, s6, v85
	v_med3_f32 v45, v89, s6, v85
	v_cvt_pk_fp8_f32 v47, v44, v45 op_sel:[0,0,1]
	v_med3_f32 v42, v42, s6, v85
	v_med3_f32 v43, v43, s6, v85
	v_mov_b32_e32 v44, 0
	v_cvt_pk_fp8_f32 v44, v42, v43
	v_med3_f32 v38, v38, s6, v85
	v_med3_f32 v39, v39, s6, v85
	v_mov_b32_e32 v42, 0
	v_cvt_pk_fp8_f32 v42, v38, v39
	v_med3_f32 v34, v34, s6, v85
	v_med3_f32 v35, v35, s6, v85
	v_med3_f32 v40, v40, s6, v85
	v_med3_f32 v41, v41, s6, v85
	v_cvt_pk_fp8_f32 v42, v34, v35 op_sel:[0,0,1]
	v_cvt_pk_fp8_f32 v44, v40, v41 op_sel:[0,0,1]
	s_cmp_lg_u32 s11, 3
	global_store_dword v[36:37], v47, off offset:256
	global_store_dword v[36:37], v44, off offset:512
	global_store_dword v[36:37], v42, off offset:768
	s_cbranch_scc1 .LBB0_1809
	v_mov_b32_e32 v76, v78
	s_nop 0
	v_and_b32_e32 v34, 3, v76
	v_mul_u32_u24_e32 v34, 0x810, v34
	v_and_b32_e32 v35, -16, v76
	v_add3_u32 v77, s87, v34, v35
	v_and_b32_e32 v34, 15, v76
	v_mul_u32_u24_e32 v34, 0x810, v34
	v_add3_u32 v94, 0, v34, v35
	ds_read_b128 v[34:37], v77 offset:33024
	ds_read_b128 v[38:41], v94
	s_waitcnt lgkmcnt(0)
	v_mfma_f32_16x16x32_bf16 v[34:37], v[34:37], v[38:41], 0
	ds_read_b128 v[38:41], v77 offset:33088
	ds_read_b128 v[42:45], v94 offset:64
	v_cmp_gt_i32_e32 vcc, 16, v76
	s_waitcnt lgkmcnt(0)
	v_mfma_f32_16x16x32_bf16 v[38:41], v[38:41], v[42:45], 0
	ds_read_b128 v[42:45], v77 offset:33152
	ds_read_b128 v[46:49], v94 offset:128
	s_waitcnt lgkmcnt(0)
	v_mfma_f32_16x16x32_bf16 v[42:45], v[42:45], v[46:49], 0
	ds_read_b128 v[46:49], v77 offset:33216
	ds_read_b128 v[86:89], v94 offset:192
	s_waitcnt lgkmcnt(0)
	v_mfma_f32_16x16x32_bf16 v[46:49], v[46:49], v[86:89], 0
	ds_read_b128 v[86:89], v77 offset:33280
	ds_read_b128 v[90:93], v94 offset:256
	s_waitcnt lgkmcnt(0)
	v_mfma_f32_16x16x32_bf16 v[34:37], v[86:89], v[90:93], v[34:37]
	ds_read_b128 v[86:89], v77 offset:33344
	ds_read_b128 v[90:93], v94 offset:320
	s_waitcnt lgkmcnt(0)
	v_mfma_f32_16x16x32_bf16 v[38:41], v[86:89], v[90:93], v[38:41]
	ds_read_b128 v[86:89], v77 offset:33408
	ds_read_b128 v[90:93], v94 offset:384
	s_waitcnt lgkmcnt(0)
	v_mfma_f32_16x16x32_bf16 v[42:45], v[86:89], v[90:93], v[42:45]
	ds_read_b128 v[86:89], v77 offset:33472
	ds_read_b128 v[90:93], v94 offset:448
	s_waitcnt lgkmcnt(0)
	v_mfma_f32_16x16x32_bf16 v[46:49], v[86:89], v[90:93], v[46:49]
	ds_read_b128 v[86:89], v77 offset:33536
	ds_read_b128 v[90:93], v94 offset:512
	s_waitcnt lgkmcnt(0)
	v_mfma_f32_16x16x32_bf16 v[34:37], v[86:89], v[90:93], v[34:37]
	ds_read_b128 v[86:89], v77 offset:33600
	ds_read_b128 v[90:93], v94 offset:576
	s_waitcnt lgkmcnt(0)
	v_mfma_f32_16x16x32_bf16 v[38:41], v[86:89], v[90:93], v[38:41]
	ds_read_b128 v[86:89], v77 offset:33664
	ds_read_b128 v[90:93], v94 offset:640
	s_waitcnt lgkmcnt(0)
	v_mfma_f32_16x16x32_bf16 v[42:45], v[86:89], v[90:93], v[42:45]
	ds_read_b128 v[86:89], v77 offset:33728
	ds_read_b128 v[90:93], v94 offset:704
	s_waitcnt lgkmcnt(0)
	v_mfma_f32_16x16x32_bf16 v[46:49], v[86:89], v[90:93], v[46:49]
	ds_read_b128 v[86:89], v77 offset:33792
	ds_read_b128 v[90:93], v94 offset:768
	s_waitcnt lgkmcnt(0)
	v_mfma_f32_16x16x32_bf16 v[34:37], v[86:89], v[90:93], v[34:37]
	ds_read_b128 v[86:89], v77 offset:33856
	ds_read_b128 v[90:93], v94 offset:832
	s_waitcnt lgkmcnt(0)
	v_mfma_f32_16x16x32_bf16 v[38:41], v[86:89], v[90:93], v[38:41]
	ds_read_b128 v[86:89], v77 offset:33920
	ds_read_b128 v[90:93], v94 offset:896
	s_waitcnt lgkmcnt(0)
	v_mfma_f32_16x16x32_bf16 v[42:45], v[86:89], v[90:93], v[42:45]
	ds_read_b128 v[86:89], v77 offset:33984
	ds_read_b128 v[90:93], v94 offset:960
	s_waitcnt lgkmcnt(0)
	v_mfma_f32_16x16x32_bf16 v[46:49], v[86:89], v[90:93], v[46:49]
	ds_read_b128 v[86:89], v77 offset:34048
	ds_read_b128 v[90:93], v94 offset:1024
	s_waitcnt lgkmcnt(0)
	v_mfma_f32_16x16x32_bf16 v[34:37], v[86:89], v[90:93], v[34:37]
	ds_read_b128 v[86:89], v77 offset:34112
	ds_read_b128 v[90:93], v94 offset:1088
	s_waitcnt lgkmcnt(0)
	v_mfma_f32_16x16x32_bf16 v[38:41], v[86:89], v[90:93], v[38:41]
	ds_read_b128 v[86:89], v77 offset:34176
	ds_read_b128 v[90:93], v94 offset:1152
	s_waitcnt lgkmcnt(0)
	v_mfma_f32_16x16x32_bf16 v[42:45], v[86:89], v[90:93], v[42:45]
	ds_read_b128 v[86:89], v77 offset:34240
	ds_read_b128 v[90:93], v94 offset:1216
	s_waitcnt lgkmcnt(0)
	v_mfma_f32_16x16x32_bf16 v[46:49], v[86:89], v[90:93], v[46:49]
	ds_read_b128 v[86:89], v77 offset:34304
	ds_read_b128 v[90:93], v94 offset:1280
	s_waitcnt lgkmcnt(0)
	v_mfma_f32_16x16x32_bf16 v[34:37], v[86:89], v[90:93], v[34:37]
	ds_read_b128 v[86:89], v77 offset:34368
	ds_read_b128 v[90:93], v94 offset:1344
	s_waitcnt lgkmcnt(0)
	v_mfma_f32_16x16x32_bf16 v[38:41], v[86:89], v[90:93], v[38:41]
	ds_read_b128 v[86:89], v77 offset:34432
	ds_read_b128 v[90:93], v94 offset:1408
	s_waitcnt lgkmcnt(0)
	v_mfma_f32_16x16x32_bf16 v[42:45], v[86:89], v[90:93], v[42:45]
	ds_read_b128 v[86:89], v77 offset:34496
	ds_read_b128 v[90:93], v94 offset:1472
	s_waitcnt lgkmcnt(0)
	v_mfma_f32_16x16x32_bf16 v[46:49], v[86:89], v[90:93], v[46:49]
	ds_read_b128 v[86:89], v77 offset:34560
	ds_read_b128 v[90:93], v94 offset:1536
	s_waitcnt lgkmcnt(0)
	v_mfma_f32_16x16x32_bf16 v[34:37], v[86:89], v[90:93], v[34:37]
	ds_read_b128 v[86:89], v77 offset:34624
	ds_read_b128 v[90:93], v94 offset:1600
	s_waitcnt lgkmcnt(0)
	v_mfma_f32_16x16x32_bf16 v[38:41], v[86:89], v[90:93], v[38:41]
	ds_read_b128 v[86:89], v77 offset:34688
	ds_read_b128 v[90:93], v94 offset:1664
	s_waitcnt lgkmcnt(0)
	v_mfma_f32_16x16x32_bf16 v[42:45], v[86:89], v[90:93], v[42:45]
	ds_read_b128 v[86:89], v77 offset:34752
	ds_read_b128 v[90:93], v94 offset:1728
	s_waitcnt lgkmcnt(0)
	v_mfma_f32_16x16x32_bf16 v[46:49], v[86:89], v[90:93], v[46:49]
	ds_read_b128 v[86:89], v77 offset:34816
	ds_read_b128 v[90:93], v94 offset:1792
	s_waitcnt lgkmcnt(0)
	v_mfma_f32_16x16x32_bf16 v[34:37], v[86:89], v[90:93], v[34:37]
	ds_read_b128 v[86:89], v77 offset:34880
	ds_read_b128 v[90:93], v94 offset:1856
	s_waitcnt lgkmcnt(0)
	v_mfma_f32_16x16x32_bf16 v[38:41], v[86:89], v[90:93], v[38:41]
	ds_read_b128 v[86:89], v77 offset:34944
	ds_read_b128 v[90:93], v94 offset:1920
	s_waitcnt lgkmcnt(0)
	v_mfma_f32_16x16x32_bf16 v[42:45], v[86:89], v[90:93], v[42:45]
	ds_read_b128 v[86:89], v77 offset:35008
	ds_read_b128 v[90:93], v94 offset:1984
	s_nop 1
	v_pk_add_f32 v[34:35], v[34:35], v[38:39]
	v_ashrrev_i32_e32 v77, 31, v76
	s_waitcnt lgkmcnt(0)
	v_mfma_f32_16x16x32_bf16 v[46:49], v[86:89], v[90:93], v[46:49]
	s_nop 7
	v_pk_add_f32 v[38:39], v[42:43], v[46:47]
	s_nop 0
	v_pk_add_f32 v[38:39], v[34:35], v[38:39]
	v_lshlrev_b64 v[34:35], 13, v[76:77]
	v_lshl_add_u64 v[34:35], s[30:31], 0, v[34:35]
	v_mov_b32_dpp v42, v38 quad_perm:[1,0,3,2] row_mask:0xf bank_mask:0xf bound_ctrl:1
	v_max_f32_e32 v42, v42, v42
	v_max_f32_e32 v42, v38, v42
	s_nop 1
	v_mov_b32_dpp v43, v42 quad_perm:[2,3,0,1] row_mask:0xf bank_mask:0xf bound_ctrl:1
	v_max_f32_e32 v43, v43, v43
	v_max_f32_e32 v42, v42, v43
	s_nop 1
	v_mov_b32_dpp v43, v42 row_half_mirror row_mask:0xf bank_mask:0xf bound_ctrl:1
	v_max_f32_e32 v43, v43, v43
	v_max_f32_e32 v42, v42, v43
	s_nop 1
	v_mov_b32_dpp v43, v42 row_mirror row_mask:0xf bank_mask:0xf bound_ctrl:1
	v_max_f32_e32 v43, v43, v43
	v_max_f32_e32 v42, v42, v43
	v_sub_f32_e32 v38, v38, v42
	v_mul_f32_e32 v38, 0x3fb8aa3b, v38
	v_exp_f32_e32 v38, v38
	s_nop 1
	v_add_f32_dpp v42, v38, v38 quad_perm:[1,0,3,2] row_mask:0xf bank_mask:0xf bound_ctrl:1
	s_nop 1
	v_add_f32_dpp v42, v42, v42 quad_perm:[2,3,0,1] row_mask:0xf bank_mask:0xf bound_ctrl:1
	s_nop 1
	v_add_f32_dpp v42, v42, v42 row_half_mirror row_mask:0xf bank_mask:0xf bound_ctrl:1
	s_nop 1
	v_mov_b32_dpp v43, v42 row_mirror row_mask:0xf bank_mask:0xf bound_ctrl:1
	s_and_saveexec_b64 s[34:35], vcc
	s_cbranch_execz .LBB0_1813
	v_add_f32_e32 v42, v42, v43
	v_rcp_f32_e32 v42, v42
	s_sub_i32 s11, s22, 24
	s_ashr_i32 s0, s11, 11
	s_ashr_i32 s1, s0, 31
	s_and_b32 s11, s11, 0x7ff
	s_lshl_b64 s[0:1], s[0:1], 17
	v_mul_f32_e32 v38, v38, v42
	v_lshl_add_u64 v[42:43], v[34:35], 0, s[0:1]
	s_lshl_b32 s26, s11, 2
	v_lshl_add_u64 v[42:43], v[42:43], 0, s[26:27]
	global_store_dword v[42:43], v38, off

.LBB0_1873:
	s_or_b64 exec, exec, s[36:37]
	v_cndmask_b32_e64 v2, -1, v3, s[54:55]
	v_cndmask_b32_e64 v12, -1, v5, s[60:61]
	v_cndmask_b32_e64 v3, -1, v6, s[62:63]
	v_cndmask_b32_e64 v6, -1, v7, s[56:57]
	v_cndmask_b32_e64 v4, -1, v8, s[50:51]
	v_cndmask_b32_e64 v7, -1, v9, s[46:47]
	v_cndmask_b32_e64 v5, -1, v10, s[42:43]
	v_cndmask_b32_e64 v8, -1, v11, s[34:35]
	s_add_i32 s5, s5, s90
	v_perm_b32 v5, v8, v5, s4
	v_perm_b32 v4, v7, v4, s4
	v_perm_b32 v3, v6, v3, s4
	v_perm_b32 v2, v12, v2, s4
	v_lshl_add_u64 v[6:7], v[18:19], 1, v[16:17]
	s_cmpk_lt_i32 s5, 0x200
	global_store_dwordx4 v[6:7], v[2:5], off
	s_waitcnt lgkmcnt(0)
	s_barrier
	s_cbranch_scc0 .LBB0_1921

.LBB0_1903:
	s_or_b64 exec, exec, s[66:67]
	v_sub_u32_e32 v2, v3, v2
	s_waitcnt lgkmcnt(0)
	v_add_u32_e32 v2, v2, v5
	v_add3_u32 v5, v2, v4, v6
	v_lshlrev_b32_e32 v4, 5, v22
	v_ashrrev_i32_e32 v3, 4, v22
	v_and_b32_e32 v4, 0x1e0, v4
	v_cmp_lt_i32_sdwa s[0:1], v5, v21 src0_sel:WORD_1 src1_sel:DWORD
	v_lshl_or_b32 v2, v3, 11, v28
	v_add_lshl_u32 v4, v4, v3, 8
	s_and_b64 s[0:1], s[60:61], s[0:1]
	v_min_i32_sdwa v3, v5, v21 dst_sel:DWORD dst_unused:UNUSED_PAD src0_sel:WORD_1 src1_sel:DWORD
	s_or_b64 s[54:55], s[54:55], s[0:1]
	v_add_u32_sdwa v3, v3, v5 dst_sel:DWORD dst_unused:UNUSED_PAD src0_sel:DWORD src1_sel:WORD_0
	s_and_saveexec_b64 s[66:67], s[54:55]
	s_cbranch_execz .LBB0_1905
	v_add_u32_e32 v6, v3, v4
	v_ashrrev_i32_e32 v7, 31, v6
	v_lshl_add_u64 v[6:7], v[6:7], 2, s[92:93]
	global_store_dword v[6:7], v2, off
.LBB0_1905:
	s_or_b64 exec, exec, s[66:67]
	v_cndmask_b32_e64 v7, 0, 1, s[60:61]
	v_add_u32_sdwa v7, v5, v7 dst_sel:DWORD dst_unused:UNUSED_PAD src0_sel:WORD_1 src1_sel:DWORD
	v_cmp_lt_i32_e64 s[60:61], v7, v21
	v_add_u32_sdwa v6, v5, v10 dst_sel:DWORD dst_unused:UNUSED_PAD src0_sel:WORD_0 src1_sel:DWORD
	s_and_b64 s[0:1], s[62:63], s[60:61]
	v_min_i32_e32 v5, v7, v21
	s_or_b64 s[60:61], s[64:65], s[0:1]
	v_add_u32_e32 v5, v5, v6
	s_and_saveexec_b64 s[66:67], s[60:61]
	s_cbranch_execz .LBB0_1907
	v_add_u32_e32 v8, v5, v4
	v_ashrrev_i32_e32 v9, 31, v8
	v_lshl_add_u64 v[8:9], v[8:9], 2, s[92:93]
	v_or_b32_e32 v10, 1, v2
	global_store_dword v[8:9], v10, off
.LBB0_1907:
	s_or_b64 exec, exec, s[66:67]
	v_cndmask_b32_e64 v8, 0, 1, s[64:65]
	v_add_u32_e32 v8, v6, v8
	v_cndmask_b32_e64 v6, 0, 1, s[62:63]
	v_add_u32_e32 v7, v7, v6
	v_cmp_lt_i32_e64 s[62:63], v7, v21
	s_and_b64 s[0:1], s[56:57], s[62:63]
	v_min_i32_e32 v6, v7, v21
	s_or_b64 s[62:63], s[58:59], s[0:1]
	v_add_u32_e32 v6, v6, v8
	s_and_saveexec_b64 s[64:65], s[62:63]
	s_cbranch_execz .LBB0_1909
	v_add_u32_e32 v10, v6, v4
	v_ashrrev_i32_e32 v11, 31, v10
	v_lshl_add_u64 v[10:11], v[10:11], 2, s[92:93]
	v_or_b32_e32 v9, 2, v2
	global_store_dword v[10:11], v9, off
.LBB0_1909:
	s_or_b64 exec, exec, s[64:65]
	v_cndmask_b32_e64 v9, 0, 1, s[58:59]
	v_add_u32_e32 v8, v8, v9
	v_cndmask_b32_e64 v9, 0, 1, s[56:57]
	v_add_u32_e32 v9, v7, v9
	v_cmp_lt_i32_e64 s[56:57], v9, v21
	s_and_b64 s[0:1], s[50:51], s[56:57]
	v_min_i32_e32 v7, v9, v21
	s_or_b64 s[56:57], s[52:53], s[0:1]
	v_add_u32_e32 v7, v7, v8
	s_and_saveexec_b64 s[58:59], s[56:57]
	s_cbranch_execz .LBB0_1911
	v_add_u32_e32 v10, v7, v4
	v_ashrrev_i32_e32 v11, 31, v10
	v_lshl_add_u64 v[10:11], v[10:11], 2, s[92:93]
	v_or_b32_e32 v12, 3, v2
	global_store_dword v[10:11], v12, off
.LBB0_1911:
	s_or_b64 exec, exec, s[58:59]
	v_cndmask_b32_e64 v10, 0, 1, s[52:53]
	v_add_u32_e32 v10, v8, v10
	v_cndmask_b32_e64 v8, 0, 1, s[50:51]
	v_add_u32_e32 v9, v9, v8
	v_cmp_lt_i32_e64 s[50:51], v9, v21
	s_and_b64 s[0:1], s[46:47], s[50:51]
	v_min_i32_e32 v8, v9, v21
	s_or_b64 s[50:51], s[48:49], s[0:1]
	v_add_u32_e32 v8, v8, v10
	s_and_saveexec_b64 s[52:53], s[50:51]
	s_cbranch_execz .LBB0_1913
	v_add_u32_e32 v22, v8, v4
	v_ashrrev_i32_e32 v23, 31, v22
	v_lshl_add_u64 v[22:23], v[22:23], 2, s[92:93]
	v_or_b32_e32 v11, 4, v2
	global_store_dword v[22:23], v11, off
.LBB0_1913:
	s_or_b64 exec, exec, s[52:53]
	v_cndmask_b32_e64 v11, 0, 1, s[48:49]
	v_add_u32_e32 v10, v10, v11
	v_cndmask_b32_e64 v11, 0, 1, s[46:47]
	v_add_u32_e32 v12, v9, v11
	v_cmp_lt_i32_e64 s[46:47], v12, v21
	s_and_b64 s[0:1], s[42:43], s[46:47]
	v_min_i32_e32 v9, v12, v21
	s_or_b64 s[46:47], s[44:45], s[0:1]
	v_add_u32_e32 v9, v9, v10
	s_and_saveexec_b64 s[48:49], s[46:47]
	s_cbranch_execz .LBB0_1915
	v_add_u32_e32 v22, v9, v4
	v_ashrrev_i32_e32 v23, 31, v22
	v_lshl_add_u64 v[22:23], v[22:23], 2, s[92:93]
	v_or_b32_e32 v11, 5, v2
	global_store_dword v[22:23], v11, off
.LBB0_1915:
	s_or_b64 exec, exec, s[48:49]
	v_cndmask_b32_e64 v11, 0, 1, s[44:45]
	v_add_u32_e32 v11, v10, v11
	v_cndmask_b32_e64 v10, 0, 1, s[42:43]
	v_add_u32_e32 v12, v12, v10
	v_cmp_lt_i32_e64 s[42:43], v12, v21
	s_and_b64 s[0:1], s[34:35], s[42:43]
	v_min_i32_e32 v10, v12, v21
	s_or_b64 s[42:43], s[38:39], s[0:1]
	v_add_u32_e32 v10, v10, v11
	s_and_saveexec_b64 s[44:45], s[42:43]
	s_cbranch_execz .LBB0_1917
	v_add_u32_e32 v22, v10, v4
	v_ashrrev_i32_e32 v23, 31, v22
	v_lshl_add_u64 v[22:23], v[22:23], 2, s[92:93]
	v_or_b32_e32 v20, 6, v2
	global_store_dword v[22:23], v20, off
.LBB0_1917:
	s_or_b64 exec, exec, s[44:45]
	v_cndmask_b32_e64 v22, 0, 1, s[34:35]
	v_add_u32_e32 v12, v12, v22
	v_cmp_lt_i32_e64 s[34:35], v12, v21
	v_cndmask_b32_e64 v20, 0, 1, s[38:39]
	s_and_b64 s[0:1], s[36:37], s[34:35]
	v_min_i32_e32 v12, v12, v21
	s_or_b64 s[34:35], s[40:41], s[0:1]
	v_add3_u32 v11, v11, v20, v12
	s_and_saveexec_b64 s[36:37], s[34:35]
	s_cbranch_execz .LBB0_1873
	v_add_u32_e32 v20, v11, v4
	v_ashrrev_i32_e32 v21, 31, v20
	v_lshl_add_u64 v[20:21], v[20:21], 2, s[92:93]
	v_or_b32_e32 v2, 7, v2
	global_store_dword v[20:21], v2, off
	s_branch .LBB0_1873

.LBB0_1978:
	s_sub_i32 s0, 0x200, s8
	s_min_i32 s11, s0, s90
	s_lshl_b32 s26, s11, 3
	s_ashr_i32 s27, s26, 31
	v_mov_b32_e32 v2, v0
	s_cmp_lt_i32 s2, s26
	s_cselect_b64 s[16:17], -1, 0
	s_cmp_ge_i32 s2, s26
	v_readfirstlane_b32 s42, v2
	s_cbranch_scc1 .LBB0_2026
	s_movk_i32 s0, 0xff
	v_cmp_lt_i32_e64 s[12:13], s0, v2
	s_movk_i32 s0, 0x100
	v_lshl_add_u32 v3, v2, 2, s95
	v_cmp_gt_i32_e64 s[14:15], s0, v2
	s_and_saveexec_b64 s[28:29], s[14:15]
	s_cbranch_execz .LBB0_1981
	s_or_b32 s0, s11, s80
	s_mul_i32 s0, s0, s76
	s_add_i32 s0, s0, s91
	s_ashr_i32 s1, s0, 31
	s_lshr_b32 s1, s1, 26
	s_add_i32 s1, s0, s1
	s_ashr_i32 s30, s1, 6
	s_lshl_b32 s30, s30, 3
	s_sub_i32 s31, s11, s30
	s_min_i32 s31, s31, 8
	s_abs_i32 s31, s31
	v_cvt_f32_u32_e32 v4, s31
	s_sub_i32 s34, 0, s31
	s_andn2_b32 s1, s1, 63
	s_sub_i32 s0, s0, s1
	v_rcp_iflag_f32_e32 v4, v4
	s_ashr_i32 s1, s0, 31
	s_abs_i32 s0, s0
	v_mul_f32_e32 v4, 0x4f7ffffe, v4
	v_cvt_u32_f32_e32 v4, v4
	s_nop 0
	v_readfirstlane_b32 s35, v4
	s_mul_i32 s34, s34, s35
	s_mul_hi_u32 s34, s35, s34
	s_add_i32 s35, s35, s34
	s_mul_hi_u32 s34, s0, s35
	s_mul_i32 s34, s34, s31
	s_sub_i32 s0, s0, s34
	s_sub_i32 s34, s0, s31
	s_cmp_ge_u32 s0, s31
	s_cselect_b32 s0, s34, s0
	s_sub_i32 s34, s0, s31
	s_cmp_ge_u32 s0, s31
	s_cselect_b32 s0, s34, s0
	s_xor_b32 s0, s0, s1
	s_sub_i32 s0, s0, s1
	s_add_i32 s1, s30, s8
	s_add_i32 s1, s1, s0
	v_lshl_add_u32 v4, s1, 8, v2
	v_ashrrev_i32_e32 v5, 31, v4
	v_lshl_add_u64 v[4:5], v[4:5], 2, s[20:21]
	global_load_dword v4, v[4:5], off
	s_waitcnt vmcnt(0) lgkmcnt(0)
	v_lshlrev_b32_e32 v4, 10, v4
	ds_write_b32 v3, v4
.LBB0_1981:
	s_or_b64 exec, exec, s[28:29]
	v_readlane_b32 s0, v254, 23
	v_mov_b64_e32 v[4:5], s[26:27]
	v_readlane_b32 s1, v254, 24
	s_nop 1
	v_cmp_ge_i64_e32 vcc, s[0:1], v[4:5]
	s_cbranch_vccnz .LBB0_2026
	s_and_saveexec_b64 s[28:29], s[14:15]
	s_cbranch_execz .LBB0_1984
	v_readlane_b32 s0, v254, 22
	s_or_b32 s0, s11, s0
	v_readlane_b32 s1, v254, 21
	s_mul_i32 s0, s0, s1
	s_add_i32 s0, s0, s89
	s_ashr_i32 s1, s0, 31
	s_lshr_b32 s1, s1, 26
	s_add_i32 s1, s0, s1
	s_ashr_i32 s30, s1, 6
	s_lshl_b32 s30, s30, 3
	s_sub_i32 s31, s11, s30
	s_min_i32 s31, s31, 8
	s_abs_i32 s31, s31
	v_cvt_f32_u32_e32 v4, s31
	s_sub_i32 s34, 0, s31
	s_andn2_b32 s1, s1, 63
	s_sub_i32 s0, s0, s1
	v_rcp_iflag_f32_e32 v4, v4
	s_ashr_i32 s1, s0, 31
	s_abs_i32 s0, s0
	v_mul_f32_e32 v4, 0x4f7ffffe, v4
	v_cvt_u32_f32_e32 v4, v4
	s_nop 0
	v_readfirstlane_b32 s35, v4
	s_mul_i32 s34, s34, s35
	s_mul_hi_u32 s34, s35, s34
	s_add_i32 s35, s35, s34
	s_mul_hi_u32 s34, s0, s35
	s_mul_i32 s34, s34, s31
	s_sub_i32 s0, s0, s34
	s_sub_i32 s34, s0, s31
	s_cmp_ge_u32 s0, s31
	s_cselect_b32 s0, s34, s0
	s_sub_i32 s34, s0, s31
	s_cmp_ge_u32 s0, s31
	s_cselect_b32 s0, s34, s0
	s_xor_b32 s0, s0, s1
	s_sub_i32 s0, s0, s1
	s_add_i32 s1, s30, s8
	s_add_i32 s1, s1, s0
	v_lshl_add_u32 v4, s1, 8, v2
	v_ashrrev_i32_e32 v5, 31, v4
	v_lshl_add_u64 v[4:5], v[4:5], 2, s[20:21]
	global_load_dword v4, v[4:5], off
	s_waitcnt vmcnt(0) lgkmcnt(0)
	v_lshlrev_b32_e32 v4, 10, v4
	ds_write_b32 v3, v4 offset:1024
.LBB0_1984:
	s_or_b64 exec, exec, s[28:29]
	v_readlane_b32 s0, v254, 28
	v_mov_b64_e32 v[4:5], s[26:27]
	v_readlane_b32 s1, v254, 29
	s_nop 1
	v_cmp_ge_i64_e32 vcc, s[0:1], v[4:5]
	s_cbranch_vccnz .LBB0_2026
	s_and_saveexec_b64 s[28:29], s[14:15]
	s_cbranch_execz .LBB0_1987
	v_readlane_b32 s0, v254, 27
	s_or_b32 s0, s11, s0
	v_readlane_b32 s1, v254, 26
	s_mul_i32 s0, s0, s1
	v_readlane_b32 s1, v254, 25
	s_add_i32 s0, s0, s1
	s_ashr_i32 s1, s0, 31
	s_lshr_b32 s1, s1, 26
	s_add_i32 s1, s0, s1
	s_ashr_i32 s30, s1, 6
	s_lshl_b32 s30, s30, 3
	s_sub_i32 s31, s11, s30
	s_min_i32 s31, s31, 8
	s_abs_i32 s31, s31
	v_cvt_f32_u32_e32 v4, s31
	s_sub_i32 s34, 0, s31
	s_andn2_b32 s1, s1, 63
	s_sub_i32 s0, s0, s1
	v_rcp_iflag_f32_e32 v4, v4
	s_ashr_i32 s1, s0, 31
	s_abs_i32 s0, s0
	v_mul_f32_e32 v4, 0x4f7ffffe, v4
	v_cvt_u32_f32_e32 v4, v4
	s_nop 0
	v_readfirstlane_b32 s35, v4
	s_mul_i32 s34, s34, s35
	s_mul_hi_u32 s34, s35, s34
	s_add_i32 s35, s35, s34
	s_mul_hi_u32 s34, s0, s35
	s_mul_i32 s34, s34, s31
	s_sub_i32 s0, s0, s34
	s_sub_i32 s34, s0, s31
	s_cmp_ge_u32 s0, s31
	s_cselect_b32 s0, s34, s0
	s_sub_i32 s34, s0, s31
	s_cmp_ge_u32 s0, s31
	s_cselect_b32 s0, s34, s0
	s_xor_b32 s0, s0, s1
	s_sub_i32 s0, s0, s1
	s_add_i32 s1, s30, s8
	s_add_i32 s1, s1, s0
	v_lshl_add_u32 v4, s1, 8, v2
	v_ashrrev_i32_e32 v5, 31, v4
	v_lshl_add_u64 v[4:5], v[4:5], 2, s[20:21]
	global_load_dword v4, v[4:5], off
	s_waitcnt vmcnt(0) lgkmcnt(0)
	v_lshlrev_b32_e32 v4, 10, v4
	ds_write_b32 v3, v4 offset:2048
.LBB0_1987:
	s_or_b64 exec, exec, s[28:29]
	v_readlane_b32 s0, v254, 33
	v_mov_b64_e32 v[4:5], s[26:27]
	v_readlane_b32 s1, v254, 34
	s_nop 1
	v_cmp_ge_i64_e32 vcc, s[0:1], v[4:5]
	s_cbranch_vccnz .LBB0_2026
	s_and_saveexec_b64 s[28:29], s[14:15]
	s_cbranch_execz .LBB0_1990
	v_readlane_b32 s0, v254, 32
	s_or_b32 s0, s11, s0
	v_readlane_b32 s1, v254, 31
	s_mul_i32 s0, s0, s1
	v_readlane_b32 s1, v254, 30
	s_add_i32 s0, s0, s1
	s_ashr_i32 s1, s0, 31
	s_lshr_b32 s1, s1, 26
	s_add_i32 s1, s0, s1
	s_ashr_i32 s30, s1, 6
	s_lshl_b32 s30, s30, 3
	s_sub_i32 s31, s11, s30
	s_min_i32 s31, s31, 8
	s_abs_i32 s31, s31
	v_cvt_f32_u32_e32 v4, s31
	s_sub_i32 s34, 0, s31
	s_andn2_b32 s1, s1, 63
	s_sub_i32 s0, s0, s1
	v_rcp_iflag_f32_e32 v4, v4
	s_ashr_i32 s1, s0, 31
	s_abs_i32 s0, s0
	v_mul_f32_e32 v4, 0x4f7ffffe, v4
	v_cvt_u32_f32_e32 v4, v4
	s_nop 0
	v_readfirstlane_b32 s35, v4
	s_mul_i32 s34, s34, s35
	s_mul_hi_u32 s34, s35, s34
	s_add_i32 s35, s35, s34
	s_mul_hi_u32 s34, s0, s35
	s_mul_i32 s34, s34, s31
	s_sub_i32 s0, s0, s34
	s_sub_i32 s34, s0, s31
	s_cmp_ge_u32 s0, s31
	s_cselect_b32 s0, s34, s0
	s_sub_i32 s34, s0, s31
	s_cmp_ge_u32 s0, s31
	s_cselect_b32 s0, s34, s0
	s_xor_b32 s0, s0, s1
	s_sub_i32 s0, s0, s1
	s_add_i32 s1, s30, s8
	s_add_i32 s1, s1, s0
	v_lshl_add_u32 v4, s1, 8, v2
	v_ashrrev_i32_e32 v5, 31, v4
	v_lshl_add_u64 v[4:5], v[4:5], 2, s[20:21]
	global_load_dword v4, v[4:5], off
	s_waitcnt vmcnt(0) lgkmcnt(0)
	v_lshlrev_b32_e32 v4, 10, v4
	ds_write_b32 v3, v4 offset:3072
.LBB0_1990:
	s_or_b64 exec, exec, s[28:29]
	v_readlane_b32 s0, v254, 38
	v_mov_b64_e32 v[4:5], s[26:27]
	v_readlane_b32 s1, v254, 39
	s_nop 1
	v_cmp_ge_i64_e32 vcc, s[0:1], v[4:5]
	s_cbranch_vccnz .LBB0_2026
	s_and_saveexec_b64 s[28:29], s[14:15]
	s_cbranch_execz .LBB0_1993
	v_readlane_b32 s0, v254, 37
	s_or_b32 s0, s11, s0
	v_readlane_b32 s1, v254, 36
	s_mul_i32 s0, s0, s1
	v_readlane_b32 s1, v254, 35
	s_add_i32 s0, s0, s1
	s_ashr_i32 s1, s0, 31
	s_lshr_b32 s1, s1, 26
	s_add_i32 s1, s0, s1
	s_ashr_i32 s30, s1, 6
	s_lshl_b32 s30, s30, 3
	s_sub_i32 s31, s11, s30
	s_min_i32 s31, s31, 8
	s_abs_i32 s31, s31
	v_cvt_f32_u32_e32 v4, s31
	s_sub_i32 s34, 0, s31
	s_andn2_b32 s1, s1, 63
	s_sub_i32 s0, s0, s1
	v_rcp_iflag_f32_e32 v4, v4
	s_ashr_i32 s1, s0, 31
	s_abs_i32 s0, s0
	v_mul_f32_e32 v4, 0x4f7ffffe, v4
	v_cvt_u32_f32_e32 v4, v4
	s_nop 0
	v_readfirstlane_b32 s35, v4
	s_mul_i32 s34, s34, s35
	s_mul_hi_u32 s34, s35, s34
	s_add_i32 s35, s35, s34
	s_mul_hi_u32 s34, s0, s35
	s_mul_i32 s34, s34, s31
	s_sub_i32 s0, s0, s34
	s_sub_i32 s34, s0, s31
	s_cmp_ge_u32 s0, s31
	s_cselect_b32 s0, s34, s0
	s_sub_i32 s34, s0, s31
	s_cmp_ge_u32 s0, s31
	s_cselect_b32 s0, s34, s0
	s_xor_b32 s0, s0, s1
	s_sub_i32 s0, s0, s1
	s_add_i32 s1, s30, s8
	s_add_i32 s1, s1, s0
	v_lshl_add_u32 v4, s1, 8, v2
	v_ashrrev_i32_e32 v5, 31, v4
	v_lshl_add_u64 v[4:5], v[4:5], 2, s[20:21]
	global_load_dword v4, v[4:5], off
	s_waitcnt vmcnt(0) lgkmcnt(0)
	v_lshlrev_b32_e32 v4, 10, v4
	ds_write_b32 v3, v4 offset:4096
.LBB0_1993:
	s_or_b64 exec, exec, s[28:29]
	v_readlane_b32 s0, v254, 43
	v_mov_b64_e32 v[4:5], s[26:27]
	v_readlane_b32 s1, v254, 44
	s_nop 1
	v_cmp_ge_i64_e32 vcc, s[0:1], v[4:5]
	s_cbranch_vccnz .LBB0_2026
	s_and_saveexec_b64 s[28:29], s[14:15]
	s_cbranch_execz .LBB0_1996
	v_readlane_b32 s0, v254, 42
	s_or_b32 s0, s11, s0
	v_readlane_b32 s1, v254, 41
	s_mul_i32 s0, s0, s1
	v_readlane_b32 s1, v254, 40
	s_add_i32 s0, s0, s1
	s_ashr_i32 s1, s0, 31
	s_lshr_b32 s1, s1, 26
	s_add_i32 s1, s0, s1
	s_ashr_i32 s30, s1, 6
	s_lshl_b32 s30, s30, 3
	s_sub_i32 s31, s11, s30
	s_min_i32 s31, s31, 8
	s_abs_i32 s31, s31
	v_cvt_f32_u32_e32 v4, s31
	s_sub_i32 s34, 0, s31
	s_andn2_b32 s1, s1, 63
	s_sub_i32 s0, s0, s1
	v_rcp_iflag_f32_e32 v4, v4
	s_ashr_i32 s1, s0, 31
	s_abs_i32 s0, s0
	v_mul_f32_e32 v4, 0x4f7ffffe, v4
	v_cvt_u32_f32_e32 v4, v4
	s_nop 0
	v_readfirstlane_b32 s35, v4
	s_mul_i32 s34, s34, s35
	s_mul_hi_u32 s34, s35, s34
	s_add_i32 s35, s35, s34
	s_mul_hi_u32 s34, s0, s35
	s_mul_i32 s34, s34, s31
	s_sub_i32 s0, s0, s34
	s_sub_i32 s34, s0, s31
	s_cmp_ge_u32 s0, s31
	s_cselect_b32 s0, s34, s0
	s_sub_i32 s34, s0, s31
	s_cmp_ge_u32 s0, s31
	s_cselect_b32 s0, s34, s0
	s_xor_b32 s0, s0, s1
	s_sub_i32 s0, s0, s1
	s_add_i32 s1, s30, s8
	s_add_i32 s1, s1, s0
	v_lshl_add_u32 v4, s1, 8, v2
	v_ashrrev_i32_e32 v5, 31, v4
	v_lshl_add_u64 v[4:5], v[4:5], 2, s[20:21]
	global_load_dword v4, v[4:5], off
	s_waitcnt vmcnt(0) lgkmcnt(0)
	v_lshlrev_b32_e32 v4, 10, v4
	ds_write_b32 v3, v4 offset:5120
.LBB0_1996:
	s_or_b64 exec, exec, s[28:29]
	v_readlane_b32 s0, v254, 48
	v_mov_b64_e32 v[4:5], s[26:27]
	v_readlane_b32 s1, v254, 49
	s_nop 1
	v_cmp_ge_i64_e32 vcc, s[0:1], v[4:5]
	s_cbranch_vccnz .LBB0_2026
	s_and_saveexec_b64 s[28:29], s[14:15]
	s_cbranch_execz .LBB0_1999
	v_readlane_b32 s0, v254, 47
	s_or_b32 s0, s11, s0
	v_readlane_b32 s1, v254, 46
	s_mul_i32 s0, s0, s1
	v_readlane_b32 s1, v254, 45
	s_add_i32 s0, s0, s1
	s_ashr_i32 s1, s0, 31
	s_lshr_b32 s1, s1, 26
	s_add_i32 s1, s0, s1
	s_ashr_i32 s30, s1, 6
	s_lshl_b32 s30, s30, 3
	s_sub_i32 s31, s11, s30
	s_min_i32 s31, s31, 8
	s_abs_i32 s31, s31
	v_cvt_f32_u32_e32 v4, s31
	s_sub_i32 s34, 0, s31
	s_andn2_b32 s1, s1, 63
	s_sub_i32 s0, s0, s1
	v_rcp_iflag_f32_e32 v4, v4
	s_ashr_i32 s1, s0, 31
	s_abs_i32 s0, s0
	v_mul_f32_e32 v4, 0x4f7ffffe, v4
	v_cvt_u32_f32_e32 v4, v4
	s_nop 0
	v_readfirstlane_b32 s35, v4
	s_mul_i32 s34, s34, s35
	s_mul_hi_u32 s34, s35, s34
	s_add_i32 s35, s35, s34
	s_mul_hi_u32 s34, s0, s35
	s_mul_i32 s34, s34, s31
	s_sub_i32 s0, s0, s34
	s_sub_i32 s34, s0, s31
	s_cmp_ge_u32 s0, s31
	s_cselect_b32 s0, s34, s0
	s_sub_i32 s34, s0, s31
	s_cmp_ge_u32 s0, s31
	s_cselect_b32 s0, s34, s0
	s_xor_b32 s0, s0, s1
	s_sub_i32 s0, s0, s1
	s_add_i32 s1, s30, s8
	s_add_i32 s1, s1, s0
	v_lshl_add_u32 v4, s1, 8, v2
	v_ashrrev_i32_e32 v5, 31, v4
	v_lshl_add_u64 v[4:5], v[4:5], 2, s[20:21]
	global_load_dword v4, v[4:5], off
	s_waitcnt vmcnt(0) lgkmcnt(0)
	v_lshlrev_b32_e32 v4, 10, v4
	ds_write_b32 v3, v4 offset:6144
.LBB0_1999:
	s_or_b64 exec, exec, s[28:29]
	v_readlane_b32 s0, v254, 53
	v_mov_b64_e32 v[4:5], s[26:27]
	v_readlane_b32 s1, v254, 54
	s_nop 1
	v_cmp_ge_i64_e32 vcc, s[0:1], v[4:5]
	s_cbranch_vccnz .LBB0_2026
	s_and_saveexec_b64 s[28:29], s[14:15]
	s_cbranch_execz .LBB0_2002
	v_readlane_b32 s0, v254, 52
	s_or_b32 s0, s11, s0
	v_readlane_b32 s1, v254, 51
	s_mul_i32 s0, s0, s1
	v_readlane_b32 s1, v254, 50
	s_add_i32 s0, s0, s1
	s_ashr_i32 s1, s0, 31
	s_lshr_b32 s1, s1, 26
	s_add_i32 s1, s0, s1
	s_ashr_i32 s30, s1, 6
	s_lshl_b32 s30, s30, 3
	s_sub_i32 s31, s11, s30
	s_min_i32 s31, s31, 8
	s_abs_i32 s31, s31
	v_cvt_f32_u32_e32 v4, s31
	s_sub_i32 s34, 0, s31
	s_andn2_b32 s1, s1, 63
	s_sub_i32 s0, s0, s1
	v_rcp_iflag_f32_e32 v4, v4
	s_ashr_i32 s1, s0, 31
	s_abs_i32 s0, s0
	v_mul_f32_e32 v4, 0x4f7ffffe, v4
	v_cvt_u32_f32_e32 v4, v4
	s_nop 0
	v_readfirstlane_b32 s35, v4
	s_mul_i32 s34, s34, s35
	s_mul_hi_u32 s34, s35, s34
	s_add_i32 s35, s35, s34
	s_mul_hi_u32 s34, s0, s35
	s_mul_i32 s34, s34, s31
	s_sub_i32 s0, s0, s34
	s_sub_i32 s34, s0, s31
	s_cmp_ge_u32 s0, s31
	s_cselect_b32 s0, s34, s0
	s_sub_i32 s34, s0, s31
	s_cmp_ge_u32 s0, s31
	s_cselect_b32 s0, s34, s0
	s_xor_b32 s0, s0, s1
	s_sub_i32 s0, s0, s1
	s_add_i32 s1, s30, s8
	s_add_i32 s1, s1, s0
	v_lshl_add_u32 v4, s1, 8, v2
	v_ashrrev_i32_e32 v5, 31, v4
	v_lshl_add_u64 v[4:5], v[4:5], 2, s[20:21]
	global_load_dword v4, v[4:5], off
	s_waitcnt vmcnt(0) lgkmcnt(0)
	v_lshlrev_b32_e32 v4, 10, v4
	ds_write_b32 v3, v4 offset:7168
.LBB0_2002:
	s_or_b64 exec, exec, s[28:29]
	v_readlane_b32 s0, v254, 58
	v_mov_b64_e32 v[4:5], s[26:27]
	v_readlane_b32 s1, v254, 59
	s_nop 1
	v_cmp_ge_i64_e32 vcc, s[0:1], v[4:5]
	s_cbranch_vccnz .LBB0_2026
	s_and_saveexec_b64 s[28:29], s[14:15]
	s_cbranch_execz .LBB0_2005
	v_readlane_b32 s0, v254, 57
	s_or_b32 s0, s11, s0
	v_readlane_b32 s1, v254, 56
	s_mul_i32 s0, s0, s1
	v_readlane_b32 s1, v254, 55
	s_add_i32 s0, s0, s1
	s_ashr_i32 s1, s0, 31
	s_lshr_b32 s1, s1, 26
	s_add_i32 s1, s0, s1
	s_ashr_i32 s30, s1, 6
	s_lshl_b32 s30, s30, 3
	s_sub_i32 s31, s11, s30
	s_min_i32 s31, s31, 8
	s_abs_i32 s31, s31
	v_cvt_f32_u32_e32 v4, s31
	s_sub_i32 s34, 0, s31
	s_andn2_b32 s1, s1, 63
	s_sub_i32 s0, s0, s1
	v_rcp_iflag_f32_e32 v4, v4
	s_ashr_i32 s1, s0, 31
	s_abs_i32 s0, s0
	v_mul_f32_e32 v4, 0x4f7ffffe, v4
	v_cvt_u32_f32_e32 v4, v4
	s_nop 0
	v_readfirstlane_b32 s35, v4
	s_mul_i32 s34, s34, s35
	s_mul_hi_u32 s34, s35, s34
	s_add_i32 s35, s35, s34
	s_mul_hi_u32 s34, s0, s35
	s_mul_i32 s34, s34, s31
	s_sub_i32 s0, s0, s34
	s_sub_i32 s34, s0, s31
	s_cmp_ge_u32 s0, s31
	s_cselect_b32 s0, s34, s0
	s_sub_i32 s34, s0, s31
	s_cmp_ge_u32 s0, s31
	s_cselect_b32 s0, s34, s0
	s_xor_b32 s0, s0, s1
	s_sub_i32 s0, s0, s1
	s_add_i32 s1, s30, s8
	s_add_i32 s1, s1, s0
	v_lshl_add_u32 v4, s1, 8, v2
	v_ashrrev_i32_e32 v5, 31, v4
	v_lshl_add_u64 v[4:5], v[4:5], 2, s[20:21]
	global_load_dword v4, v[4:5], off
	s_waitcnt vmcnt(0) lgkmcnt(0)
	v_lshlrev_b32_e32 v4, 10, v4
	ds_write_b32 v3, v4 offset:8192
.LBB0_2005:
	s_or_b64 exec, exec, s[28:29]
	v_readlane_b32 s0, v254, 63
	v_mov_b64_e32 v[4:5], s[26:27]
	v_readlane_b32 s1, v253, 0
	s_nop 1
	v_cmp_ge_i64_e32 vcc, s[0:1], v[4:5]
	s_cbranch_vccnz .LBB0_2026
	s_and_saveexec_b64 s[28:29], s[14:15]
	s_cbranch_execz .LBB0_2008
	v_readlane_b32 s0, v254, 62
	s_or_b32 s0, s11, s0
	v_readlane_b32 s1, v254, 61
	s_mul_i32 s0, s0, s1
	v_readlane_b32 s1, v254, 60
	s_add_i32 s0, s0, s1
	s_ashr_i32 s1, s0, 31
	s_lshr_b32 s1, s1, 26
	s_add_i32 s1, s0, s1
	s_ashr_i32 s30, s1, 6
	s_lshl_b32 s30, s30, 3
	s_sub_i32 s31, s11, s30
	s_min_i32 s31, s31, 8
	s_abs_i32 s31, s31
	v_cvt_f32_u32_e32 v4, s31
	s_sub_i32 s34, 0, s31
	s_andn2_b32 s1, s1, 63
	s_sub_i32 s0, s0, s1
	v_rcp_iflag_f32_e32 v4, v4
	s_ashr_i32 s1, s0, 31
	s_abs_i32 s0, s0
	v_mul_f32_e32 v4, 0x4f7ffffe, v4
	v_cvt_u32_f32_e32 v4, v4
	s_nop 0
	v_readfirstlane_b32 s35, v4
	s_mul_i32 s34, s34, s35
	s_mul_hi_u32 s34, s35, s34
	s_add_i32 s35, s35, s34
	s_mul_hi_u32 s34, s0, s35
	s_mul_i32 s34, s34, s31
	s_sub_i32 s0, s0, s34
	s_sub_i32 s34, s0, s31
	s_cmp_ge_u32 s0, s31
	s_cselect_b32 s0, s34, s0
	s_sub_i32 s34, s0, s31
	s_cmp_ge_u32 s0, s31
	s_cselect_b32 s0, s34, s0
	s_xor_b32 s0, s0, s1
	s_sub_i32 s0, s0, s1
	s_add_i32 s1, s30, s8
	s_add_i32 s1, s1, s0
	v_lshl_add_u32 v4, s1, 8, v2
	v_ashrrev_i32_e32 v5, 31, v4
	v_lshl_add_u64 v[4:5], v[4:5], 2, s[20:21]
	global_load_dword v4, v[4:5], off
	s_waitcnt vmcnt(0) lgkmcnt(0)
	v_lshlrev_b32_e32 v4, 10, v4
	ds_write_b32 v3, v4 offset:9216
.LBB0_2008:
	s_or_b64 exec, exec, s[28:29]
	v_readlane_b32 s0, v253, 4
	v_mov_b64_e32 v[4:5], s[26:27]
	v_readlane_b32 s1, v253, 5
	s_nop 1
	v_cmp_ge_i64_e32 vcc, s[0:1], v[4:5]
	s_cbranch_vccnz .LBB0_2026
	s_and_saveexec_b64 s[28:29], s[14:15]
	s_cbranch_execz .LBB0_2011
	v_readlane_b32 s0, v253, 3
	s_or_b32 s0, s11, s0
	v_readlane_b32 s1, v253, 2
	s_mul_i32 s0, s0, s1
	v_readlane_b32 s1, v253, 1
	s_add_i32 s0, s0, s1
	s_ashr_i32 s1, s0, 31
	s_lshr_b32 s1, s1, 26
	s_add_i32 s1, s0, s1
	s_ashr_i32 s30, s1, 6
	s_lshl_b32 s30, s30, 3
	s_sub_i32 s31, s11, s30
	s_min_i32 s31, s31, 8
	s_abs_i32 s31, s31
	v_cvt_f32_u32_e32 v4, s31
	s_sub_i32 s34, 0, s31
	s_andn2_b32 s1, s1, 63
	s_sub_i32 s0, s0, s1
	v_rcp_iflag_f32_e32 v4, v4
	s_ashr_i32 s1, s0, 31
	s_abs_i32 s0, s0
	v_mul_f32_e32 v4, 0x4f7ffffe, v4
	v_cvt_u32_f32_e32 v4, v4
	s_nop 0
	v_readfirstlane_b32 s35, v4
	s_mul_i32 s34, s34, s35
	s_mul_hi_u32 s34, s35, s34
	s_add_i32 s35, s35, s34
	s_mul_hi_u32 s34, s0, s35
	s_mul_i32 s34, s34, s31
	s_sub_i32 s0, s0, s34
	s_sub_i32 s34, s0, s31
	s_cmp_ge_u32 s0, s31
	s_cselect_b32 s0, s34, s0
	s_sub_i32 s34, s0, s31
	s_cmp_ge_u32 s0, s31
	s_cselect_b32 s0, s34, s0
	s_xor_b32 s0, s0, s1
	s_sub_i32 s0, s0, s1
	s_add_i32 s1, s30, s8
	s_add_i32 s1, s1, s0
	v_lshl_add_u32 v4, s1, 8, v2
	v_ashrrev_i32_e32 v5, 31, v4
	v_lshl_add_u64 v[4:5], v[4:5], 2, s[20:21]
	global_load_dword v4, v[4:5], off
	s_waitcnt vmcnt(0) lgkmcnt(0)
	v_lshlrev_b32_e32 v4, 10, v4
	ds_write_b32 v3, v4 offset:10240
.LBB0_2011:
	s_or_b64 exec, exec, s[28:29]
	v_readlane_b32 s0, v253, 9
	v_mov_b64_e32 v[4:5], s[26:27]
	v_readlane_b32 s1, v253, 10
	s_nop 1
	v_cmp_ge_i64_e32 vcc, s[0:1], v[4:5]
	s_cbranch_vccnz .LBB0_2026
	s_and_saveexec_b64 s[28:29], s[14:15]
	s_cbranch_execz .LBB0_2014
	v_readlane_b32 s0, v253, 8
	s_or_b32 s0, s11, s0
	v_readlane_b32 s1, v253, 7
	s_mul_i32 s0, s0, s1
	v_readlane_b32 s1, v253, 6
	s_add_i32 s0, s0, s1
	s_ashr_i32 s1, s0, 31
	s_lshr_b32 s1, s1, 26
	s_add_i32 s1, s0, s1
	s_ashr_i32 s30, s1, 6
	s_lshl_b32 s30, s30, 3
	s_sub_i32 s31, s11, s30
	s_min_i32 s31, s31, 8
	s_abs_i32 s31, s31
	v_cvt_f32_u32_e32 v4, s31
	s_sub_i32 s34, 0, s31
	s_andn2_b32 s1, s1, 63
	s_sub_i32 s0, s0, s1
	v_rcp_iflag_f32_e32 v4, v4
	s_ashr_i32 s1, s0, 31
	s_abs_i32 s0, s0
	v_mul_f32_e32 v4, 0x4f7ffffe, v4
	v_cvt_u32_f32_e32 v4, v4
	s_nop 0
	v_readfirstlane_b32 s35, v4
	s_mul_i32 s34, s34, s35
	s_mul_hi_u32 s34, s35, s34
	s_add_i32 s35, s35, s34
	s_mul_hi_u32 s34, s0, s35
	s_mul_i32 s34, s34, s31
	s_sub_i32 s0, s0, s34
	s_sub_i32 s34, s0, s31
	s_cmp_ge_u32 s0, s31
	s_cselect_b32 s0, s34, s0
	s_sub_i32 s34, s0, s31
	s_cmp_ge_u32 s0, s31
	s_cselect_b32 s0, s34, s0
	s_xor_b32 s0, s0, s1
	s_sub_i32 s0, s0, s1
	s_add_i32 s1, s30, s8
	s_add_i32 s1, s1, s0
	v_lshl_add_u32 v4, s1, 8, v2
	v_ashrrev_i32_e32 v5, 31, v4
	v_lshl_add_u64 v[4:5], v[4:5], 2, s[20:21]
	global_load_dword v4, v[4:5], off
	s_waitcnt vmcnt(0) lgkmcnt(0)
	v_lshlrev_b32_e32 v4, 10, v4
	ds_write_b32 v3, v4 offset:11264
.LBB0_2014:
	s_or_b64 exec, exec, s[28:29]
	v_readlane_b32 s0, v253, 14
	v_mov_b64_e32 v[4:5], s[26:27]
	v_readlane_b32 s1, v253, 15
	s_nop 1
	v_cmp_ge_i64_e32 vcc, s[0:1], v[4:5]
	s_cbranch_vccnz .LBB0_2026
	s_and_saveexec_b64 s[28:29], s[14:15]
	s_cbranch_execz .LBB0_2017
	v_readlane_b32 s0, v253, 13
	s_or_b32 s0, s11, s0
	v_readlane_b32 s1, v253, 12
	s_mul_i32 s0, s0, s1
	v_readlane_b32 s1, v253, 11
	s_add_i32 s0, s0, s1
	s_ashr_i32 s1, s0, 31
	s_lshr_b32 s1, s1, 26
	s_add_i32 s1, s0, s1
	s_ashr_i32 s30, s1, 6
	s_lshl_b32 s30, s30, 3
	s_sub_i32 s31, s11, s30
	s_min_i32 s31, s31, 8
	s_abs_i32 s31, s31
	v_cvt_f32_u32_e32 v4, s31
	s_sub_i32 s34, 0, s31
	s_andn2_b32 s1, s1, 63
	s_sub_i32 s0, s0, s1
	v_rcp_iflag_f32_e32 v4, v4
	s_ashr_i32 s1, s0, 31
	s_abs_i32 s0, s0
	v_mul_f32_e32 v4, 0x4f7ffffe, v4
	v_cvt_u32_f32_e32 v4, v4
	s_nop 0
	v_readfirstlane_b32 s35, v4
	s_mul_i32 s34, s34, s35
	s_mul_hi_u32 s34, s35, s34
	s_add_i32 s35, s35, s34
	s_mul_hi_u32 s34, s0, s35
	s_mul_i32 s34, s34, s31
	s_sub_i32 s0, s0, s34
	s_sub_i32 s34, s0, s31
	s_cmp_ge_u32 s0, s31
	s_cselect_b32 s0, s34, s0
	s_sub_i32 s34, s0, s31
	s_cmp_ge_u32 s0, s31
	s_cselect_b32 s0, s34, s0
	s_xor_b32 s0, s0, s1
	s_sub_i32 s0, s0, s1
	s_add_i32 s1, s30, s8
	s_add_i32 s1, s1, s0
	v_lshl_add_u32 v4, s1, 8, v2
	v_ashrrev_i32_e32 v5, 31, v4
	v_lshl_add_u64 v[4:5], v[4:5], 2, s[20:21]
	global_load_dword v4, v[4:5], off
	s_waitcnt vmcnt(0) lgkmcnt(0)
	v_lshlrev_b32_e32 v4, 10, v4
	ds_write_b32 v3, v4 offset:12288
.LBB0_2017:
	s_or_b64 exec, exec, s[28:29]
	v_readlane_b32 s0, v253, 19
	v_mov_b64_e32 v[4:5], s[26:27]
	v_readlane_b32 s1, v253, 20
	s_nop 1
	v_cmp_ge_i64_e32 vcc, s[0:1], v[4:5]
	s_cbranch_vccnz .LBB0_2026
	s_and_saveexec_b64 s[28:29], s[14:15]
	s_cbranch_execz .LBB0_2020
	v_readlane_b32 s0, v253, 18
	s_or_b32 s0, s11, s0
	v_readlane_b32 s1, v253, 17
	s_mul_i32 s0, s0, s1
	v_readlane_b32 s1, v253, 16
	s_add_i32 s0, s0, s1
	s_ashr_i32 s1, s0, 31
	s_lshr_b32 s1, s1, 26
	s_add_i32 s1, s0, s1
	s_ashr_i32 s30, s1, 6
	s_lshl_b32 s30, s30, 3
	s_sub_i32 s31, s11, s30
	s_min_i32 s31, s31, 8
	s_abs_i32 s31, s31
	v_cvt_f32_u32_e32 v4, s31
	s_sub_i32 s34, 0, s31
	s_andn2_b32 s1, s1, 63
	s_sub_i32 s0, s0, s1
	v_rcp_iflag_f32_e32 v4, v4
	s_ashr_i32 s1, s0, 31
	s_abs_i32 s0, s0
	v_mul_f32_e32 v4, 0x4f7ffffe, v4
	v_cvt_u32_f32_e32 v4, v4
	s_nop 0
	v_readfirstlane_b32 s35, v4
	s_mul_i32 s34, s34, s35
	s_mul_hi_u32 s34, s35, s34
	s_add_i32 s35, s35, s34
	s_mul_hi_u32 s34, s0, s35
	s_mul_i32 s34, s34, s31
	s_sub_i32 s0, s0, s34
	s_sub_i32 s34, s0, s31
	s_cmp_ge_u32 s0, s31
	s_cselect_b32 s0, s34, s0
	s_sub_i32 s34, s0, s31
	s_cmp_ge_u32 s0, s31
	s_cselect_b32 s0, s34, s0
	s_xor_b32 s0, s0, s1
	s_sub_i32 s0, s0, s1
	s_add_i32 s1, s30, s8
	s_add_i32 s1, s1, s0
	v_lshl_add_u32 v4, s1, 8, v2
	v_ashrrev_i32_e32 v5, 31, v4
	v_lshl_add_u64 v[4:5], v[4:5], 2, s[20:21]
	global_load_dword v4, v[4:5], off
	s_waitcnt vmcnt(0) lgkmcnt(0)
	v_lshlrev_b32_e32 v4, 10, v4
	ds_write_b32 v3, v4 offset:13312
.LBB0_2020:
	s_or_b64 exec, exec, s[28:29]
	v_readlane_b32 s0, v253, 24
	v_mov_b64_e32 v[4:5], s[26:27]
	v_readlane_b32 s1, v253, 25
	s_nop 1
	v_cmp_ge_i64_e32 vcc, s[0:1], v[4:5]
	s_cbranch_vccnz .LBB0_2026
	s_and_saveexec_b64 s[28:29], s[14:15]
	s_cbranch_execz .LBB0_2023
	v_readlane_b32 s0, v253, 23
	s_or_b32 s0, s11, s0
	v_readlane_b32 s1, v253, 22
	s_mul_i32 s0, s0, s1
	v_readlane_b32 s1, v253, 21
	s_add_i32 s0, s0, s1
	s_ashr_i32 s1, s0, 31
	s_lshr_b32 s1, s1, 26
	s_add_i32 s1, s0, s1
	s_ashr_i32 s14, s1, 6
	s_lshl_b32 s14, s14, 3
	s_sub_i32 s15, s11, s14
	s_min_i32 s15, s15, 8
	s_abs_i32 s15, s15
	v_cvt_f32_u32_e32 v4, s15
	s_sub_i32 s30, 0, s15
	s_andn2_b32 s1, s1, 63
	s_sub_i32 s0, s0, s1
	v_rcp_iflag_f32_e32 v4, v4
	s_ashr_i32 s1, s0, 31
	s_abs_i32 s0, s0
	v_mul_f32_e32 v4, 0x4f7ffffe, v4
	v_cvt_u32_f32_e32 v4, v4
	s_nop 0
	v_readfirstlane_b32 s31, v4
	s_mul_i32 s30, s30, s31
	s_mul_hi_u32 s30, s31, s30
	s_add_i32 s31, s31, s30
	s_mul_hi_u32 s30, s0, s31
	s_mul_i32 s30, s30, s15
	s_sub_i32 s0, s0, s30
	s_sub_i32 s30, s0, s15
	s_cmp_ge_u32 s0, s15
	s_cselect_b32 s0, s30, s0
	s_sub_i32 s30, s0, s15
	s_cmp_ge_u32 s0, s15
	s_cselect_b32 s0, s30, s0
	s_xor_b32 s0, s0, s1
	s_sub_i32 s0, s0, s1
	s_add_i32 s1, s14, s8
	s_add_i32 s1, s1, s0
	v_lshl_add_u32 v4, s1, 8, v2
	v_ashrrev_i32_e32 v5, 31, v4
	v_lshl_add_u64 v[4:5], v[4:5], 2, s[20:21]
	global_load_dword v4, v[4:5], off
	s_waitcnt vmcnt(0) lgkmcnt(0)
	v_lshlrev_b32_e32 v4, 10, v4
	ds_write_b32 v3, v4 offset:14336
.LBB0_2023:
	s_or_b64 exec, exec, s[28:29]
	v_readlane_b32 s0, v253, 27
	v_mov_b64_e32 v[4:5], s[26:27]
	v_readlane_b32 s1, v253, 28
	s_nop 1
	v_cmp_lt_i64_e32 vcc, s[0:1], v[4:5]
	s_xor_b64 s[0:1], s[12:13], -1
	s_and_b64 s[0:1], vcc, s[0:1]
	s_and_saveexec_b64 s[12:13], s[0:1]
	s_cbranch_execz .LBB0_2025
	v_readlane_b32 s0, v253, 30
	s_or_b32 s0, s11, s0
	v_readlane_b32 s1, v253, 29
	s_mul_i32 s0, s0, s1
	v_readlane_b32 s1, v253, 26
	s_add_i32 s0, s0, s1
	s_ashr_i32 s1, s0, 31
	s_lshr_b32 s1, s1, 26
	s_add_i32 s1, s0, s1
	s_ashr_i32 s14, s1, 6
	s_lshl_b32 s14, s14, 3
	s_sub_i32 s15, s11, s14
	s_min_i32 s15, s15, 8
	s_abs_i32 s15, s15
	v_cvt_f32_u32_e32 v4, s15
	s_sub_i32 s28, 0, s15
	s_andn2_b32 s1, s1, 63
	s_sub_i32 s0, s0, s1
	v_rcp_iflag_f32_e32 v4, v4
	s_ashr_i32 s1, s0, 31
	s_abs_i32 s0, s0
	v_mul_f32_e32 v4, 0x4f7ffffe, v4
	v_cvt_u32_f32_e32 v4, v4
	s_nop 0
	v_readfirstlane_b32 s29, v4
	s_mul_i32 s28, s28, s29
	s_mul_hi_u32 s28, s29, s28
	s_add_i32 s29, s29, s28
	s_mul_hi_u32 s28, s0, s29
	s_mul_i32 s28, s28, s15
	s_sub_i32 s0, s0, s28
	s_sub_i32 s28, s0, s15
	s_cmp_ge_u32 s0, s15
	s_cselect_b32 s0, s28, s0
	s_sub_i32 s28, s0, s15
	s_cmp_ge_u32 s0, s15
	s_cselect_b32 s0, s28, s0
	s_xor_b32 s0, s0, s1
	s_sub_i32 s0, s0, s1
	s_add_i32 s1, s14, s8
	s_add_i32 s1, s1, s0
	v_lshl_add_u32 v4, s1, 8, v2
	v_ashrrev_i32_e32 v5, 31, v4
	v_lshl_add_u64 v[4:5], v[4:5], 2, s[20:21]
	global_load_dword v4, v[4:5], off
	s_waitcnt vmcnt(0) lgkmcnt(0)
	v_lshlrev_b32_e32 v4, 10, v4
	ds_write_b32 v3, v4 offset:15360

.LBB0_2041:
	s_add_u32 s14, s38, 0x100
	s_addc_u32 s15, s39, 0
	s_add_u32 s36, s35, s38
	s_addc_u32 s37, s55, s39
	s_cmpk_eq_i32 s38, 0x300
	s_cselect_b64 vcc, -1, 0
	s_and_b64 s[0:1], vcc, exec
	s_cselect_b32 s1, 0, s14
	s_cselect_b32 s0, 0, s15
	s_cselect_b32 s36, s31, s36
	s_cselect_b32 s37, s29, s37
	s_add_u32 s40, s18, s1
	s_addc_u32 s41, s19, s0
	s_add_i32 s1, 0, 0x10000
	v_add_u32_e32 v14, s1, v197
	ds_read_b128 v[2:5], v14
	ds_read_b128 v[6:9], v14 offset:1024
	ds_read_b128 v[10:13], v14 offset:2048
	ds_read_b128 v[14:17], v14 offset:3072
	v_cndmask_b32_e32 v162, v168, v171, vcc
	v_cndmask_b32_e32 v184, v170, v198, vcc
	v_cndmask_b32_e32 v175, v172, v199, vcc
	v_cndmask_b32_e32 v173, v174, v200, vcc
	v_lshl_add_u64 v[18:19], v[178:179], 0, s[38:39]
	s_add_i32 m0, s45, 0xc000
	ds_read_b128 v[202:205], v169
	ds_read_b128 v[206:209], v169 offset:1024
	ds_read_b128 v[210:213], v169 offset:2048
	ds_read_b128 v[214:217], v169 offset:3072
	ds_read_b128 v[218:221], v169 offset:4096
	ds_read_b128 v[222:225], v169 offset:5120
	ds_read_b128 v[226:229], v169 offset:6144
	ds_read_b128 v[230:233], v169 offset:7168
	global_load_lds_dwordx4 v[18:19], off
	v_lshl_add_u64 v[18:19], v[176:177], 0, s[38:39]
	s_add_i32 m0, s45, 0xe000
	s_nop 0
	global_load_lds_dwordx4 v[18:19], off
	s_waitcnt lgkmcnt(8)
	s_waitcnt vmcnt(10)
	s_barrier
	s_waitcnt lgkmcnt(0)
	s_waitcnt lgkmcnt(0)
	v_mfma_scale_f32_16x16x128_f8f6f4 v[158:161], v[2:9], v[202:209], v[158:161], v188, v188 op_sel_hi:[0,0,0]
	v_mfma_scale_f32_16x16x128_f8f6f4 v[150:153], v[10:17], v[202:209], v[150:153], v188, v188 op_sel_hi:[0,0,0]
	v_mfma_scale_f32_16x16x128_f8f6f4 v[142:145], v[2:9], v[210:217], v[142:145], v188, v188 op_sel_hi:[0,0,0]
	v_mfma_scale_f32_16x16x128_f8f6f4 v[134:137], v[10:17], v[210:217], v[134:137], v188, v188 op_sel_hi:[0,0,0]
	v_mfma_scale_f32_16x16x128_f8f6f4 v[126:129], v[2:9], v[218:225], v[126:129], v188, v188 op_sel_hi:[0,0,0]
	v_mfma_scale_f32_16x16x128_f8f6f4 v[118:121], v[10:17], v[218:225], v[118:121], v188, v188 op_sel_hi:[0,0,0]
	v_mfma_scale_f32_16x16x128_f8f6f4 v[110:113], v[2:9], v[226:233], v[110:113], v188, v188 op_sel_hi:[0,0,0]
	v_mfma_scale_f32_16x16x128_f8f6f4 v[102:105], v[10:17], v[226:233], v[102:105], v188, v188 op_sel_hi:[0,0,0]
	s_barrier
	s_add_i32 s0, 0, 0x14000
	s_add_i32 s1, s1, s43
	v_add_u32_e32 v30, s0, v197
	v_lshl_add_u64 v[180:181], s[36:37], 0, v[164:165]
	s_mov_b32 m0, s1
	ds_read_b128 v[18:21], v30
	ds_read_b128 v[22:25], v30 offset:1024
	ds_read_b128 v[26:29], v30 offset:2048
	ds_read_b128 v[30:33], v30 offset:3072
	global_load_lds_dwordx4 v[180:181], off
	v_lshl_add_u64 v[182:183], s[36:37], 0, v[166:167]
	s_add_i32 m0, s1, 0x2000
	s_nop 0
	global_load_lds_dwordx4 v[182:183], off
	s_waitcnt vmcnt(10)
	s_barrier
	s_waitcnt lgkmcnt(0)
	s_waitcnt lgkmcnt(0)
	v_mfma_scale_f32_16x16x128_f8f6f4 v[154:157], v[18:25], v[202:209], v[154:157], v188, v188 op_sel_hi:[0,0,0]
	v_mfma_scale_f32_16x16x128_f8f6f4 v[146:149], v[26:33], v[202:209], v[146:149], v188, v188 op_sel_hi:[0,0,0]
	v_mfma_scale_f32_16x16x128_f8f6f4 v[138:141], v[18:25], v[210:217], v[138:141], v188, v188 op_sel_hi:[0,0,0]
	v_mfma_scale_f32_16x16x128_f8f6f4 v[130:133], v[26:33], v[210:217], v[130:133], v188, v188 op_sel_hi:[0,0,0]
	v_mfma_scale_f32_16x16x128_f8f6f4 v[122:125], v[18:25], v[218:225], v[122:125], v188, v188 op_sel_hi:[0,0,0]
	v_mfma_scale_f32_16x16x128_f8f6f4 v[114:117], v[26:33], v[218:225], v[114:117], v188, v188 op_sel_hi:[0,0,0]
	v_mfma_scale_f32_16x16x128_f8f6f4 v[106:109], v[18:25], v[226:233], v[106:109], v188, v188 op_sel_hi:[0,0,0]
	v_mfma_scale_f32_16x16x128_f8f6f4 v[98:101], v[26:33], v[226:233], v[98:101], v188, v188 op_sel_hi:[0,0,0]
	s_mov_b32 m0, s45
	s_barrier
	ds_read_b128 v[202:205], v169 offset:16384
	ds_read_b128 v[206:209], v169 offset:17408
	ds_read_b128 v[210:213], v169 offset:18432
	ds_read_b128 v[214:217], v169 offset:19456
	ds_read_b128 v[218:221], v169 offset:20480
	ds_read_b128 v[222:225], v169 offset:21504
	ds_read_b128 v[226:229], v169 offset:22528
	ds_read_b128 v[230:233], v169 offset:23552
	global_load_lds_dwordx4 v162, s[40:41]
	s_mov_b32 m0, s46
	v_mov_b32_e32 v185, v163
	global_load_lds_dwordx4 v184, s[40:41]
	s_waitcnt vmcnt(10)
	s_barrier
	s_waitcnt lgkmcnt(0)
	v_lshl_add_u64 v[186:187], s[40:41], 0, v[162:163]
	v_lshl_add_u64 v[184:185], s[40:41], 0, v[184:185]
	s_waitcnt lgkmcnt(0)
	v_mfma_scale_f32_16x16x128_f8f6f4 v[94:97], v[2:9], v[202:209], v[94:97], v188, v188 op_sel_hi:[0,0,0]
	v_mfma_scale_f32_16x16x128_f8f6f4 v[86:89], v[10:17], v[202:209], v[86:89], v188, v188 op_sel_hi:[0,0,0]
	v_mfma_scale_f32_16x16x128_f8f6f4 v[78:81], v[2:9], v[210:217], v[78:81], v188, v188 op_sel_hi:[0,0,0]
	v_mfma_scale_f32_16x16x128_f8f6f4 v[70:73], v[10:17], v[210:217], v[70:73], v188, v188 op_sel_hi:[0,0,0]
	v_mfma_scale_f32_16x16x128_f8f6f4 v[62:65], v[2:9], v[218:225], v[62:65], v188, v188 op_sel_hi:[0,0,0]
	v_mfma_scale_f32_16x16x128_f8f6f4 v[54:57], v[10:17], v[218:225], v[54:57], v188, v188 op_sel_hi:[0,0,0]
	v_mfma_scale_f32_16x16x128_f8f6f4 v[46:49], v[2:9], v[226:233], v[46:49], v188, v188 op_sel_hi:[0,0,0]
	v_mfma_scale_f32_16x16x128_f8f6f4 v[38:41], v[10:17], v[226:233], v[38:41], v188, v188 op_sel_hi:[0,0,0]
	s_barrier
	s_add_u32 s38, s36, 0x20000
	s_addc_u32 s39, s37, 0
	s_add_i32 s0, s0, s43
	v_lshl_add_u64 v[2:3], s[38:39], 0, v[164:165]
	s_mov_b32 m0, s0
	s_nop 0
	global_load_lds_dwordx4 v[2:3], off
	v_lshl_add_u64 v[2:3], s[38:39], 0, v[166:167]
	s_add_i32 m0, s0, 0x2000
	s_nop 0
	global_load_lds_dwordx4 v[2:3], off
	s_waitcnt vmcnt(10)
	s_barrier
	v_mfma_scale_f32_16x16x128_f8f6f4 v[90:93], v[18:25], v[202:209], v[90:93], v188, v188 op_sel_hi:[0,0,0]
	v_mfma_scale_f32_16x16x128_f8f6f4 v[82:85], v[26:33], v[202:209], v[82:85], v188, v188 op_sel_hi:[0,0,0]
	v_mfma_scale_f32_16x16x128_f8f6f4 v[74:77], v[18:25], v[210:217], v[74:77], v188, v188 op_sel_hi:[0,0,0]
	v_mfma_scale_f32_16x16x128_f8f6f4 v[66:69], v[26:33], v[210:217], v[66:69], v188, v188 op_sel_hi:[0,0,0]
	v_mfma_scale_f32_16x16x128_f8f6f4 v[58:61], v[18:25], v[218:225], v[58:61], v188, v188 op_sel_hi:[0,0,0]
	v_mfma_scale_f32_16x16x128_f8f6f4 v[50:53], v[26:33], v[218:225], v[50:53], v188, v188 op_sel_hi:[0,0,0]
	v_mfma_scale_f32_16x16x128_f8f6f4 v[42:45], v[18:25], v[226:233], v[42:45], v188, v188 op_sel_hi:[0,0,0]
	v_mfma_scale_f32_16x16x128_f8f6f4 v[34:37], v[26:33], v[226:233], v[34:37], v188, v188 op_sel_hi:[0,0,0]
	s_add_i32 s0, 0, 0x18000
	v_add_u32_e32 v14, s0, v197
	s_barrier
	ds_read_b128 v[2:5], v14
	ds_read_b128 v[6:9], v14 offset:1024
	ds_read_b128 v[10:13], v14 offset:2048
	ds_read_b128 v[14:17], v14 offset:3072
	s_mov_b32 m0, s47
	ds_read_b128 v[18:21], v169 offset:32768
	ds_read_b128 v[22:25], v169 offset:33792
	ds_read_b128 v[26:29], v169 offset:34816
	ds_read_b128 v[30:33], v169 offset:35840
	ds_read_b128 v[202:205], v169 offset:36864
	ds_read_b128 v[206:209], v169 offset:37888
	ds_read_b128 v[210:213], v169 offset:38912
	ds_read_b128 v[214:217], v169 offset:39936
	global_load_lds_dwordx4 v175, s[40:41]
	s_mov_b32 m0, s48
	s_nop 0
	global_load_lds_dwordx4 v173, s[40:41]
	s_waitcnt lgkmcnt(8)
	s_waitcnt vmcnt(10)
	s_barrier
	s_waitcnt lgkmcnt(0)
	s_waitcnt lgkmcnt(0)
	v_mfma_scale_f32_16x16x128_f8f6f4 v[158:161], v[2:9], v[18:25], v[158:161], v188, v188 op_sel_hi:[0,0,0]
	v_mfma_scale_f32_16x16x128_f8f6f4 v[150:153], v[10:17], v[18:25], v[150:153], v188, v188 op_sel_hi:[0,0,0]
	v_mfma_scale_f32_16x16x128_f8f6f4 v[142:145], v[2:9], v[26:33], v[142:145], v188, v188 op_sel_hi:[0,0,0]
	v_mfma_scale_f32_16x16x128_f8f6f4 v[134:137], v[10:17], v[26:33], v[134:137], v188, v188 op_sel_hi:[0,0,0]
	v_mfma_scale_f32_16x16x128_f8f6f4 v[126:129], v[2:9], v[202:209], v[126:129], v188, v188 op_sel_hi:[0,0,0]
	v_mfma_scale_f32_16x16x128_f8f6f4 v[118:121], v[10:17], v[202:209], v[118:121], v188, v188 op_sel_hi:[0,0,0]
	v_mfma_scale_f32_16x16x128_f8f6f4 v[110:113], v[2:9], v[210:217], v[110:113], v188, v188 op_sel_hi:[0,0,0]
	v_mfma_scale_f32_16x16x128_f8f6f4 v[102:105], v[10:17], v[210:217], v[102:105], v188, v188 op_sel_hi:[0,0,0]
	s_barrier
	s_add_i32 s38, 0, 0x1c000
	s_add_i32 s0, s0, s43
	v_add_u32_e32 v162, s38, v197
	v_lshl_add_u64 v[180:181], v[180:181], 0, s[24:25]
	s_mov_b32 m0, s0
	ds_read_b128 v[218:221], v162
	ds_read_b128 v[222:225], v162 offset:1024
	ds_read_b128 v[226:229], v162 offset:2048
	ds_read_b128 v[230:233], v162 offset:3072
	global_load_lds_dwordx4 v[180:181], off
	v_lshl_add_u64 v[180:181], v[182:183], 0, s[24:25]
	s_add_i32 m0, s0, 0x2000
	s_nop 0
	global_load_lds_dwordx4 v[180:181], off
	s_waitcnt vmcnt(10)
	s_barrier
	s_waitcnt lgkmcnt(0)
	s_waitcnt lgkmcnt(0)
	v_mfma_scale_f32_16x16x128_f8f6f4 v[154:157], v[218:225], v[18:25], v[154:157], v188, v188 op_sel_hi:[0,0,0]
	v_mfma_scale_f32_16x16x128_f8f6f4 v[146:149], v[226:233], v[18:25], v[146:149], v188, v188 op_sel_hi:[0,0,0]
	v_mfma_scale_f32_16x16x128_f8f6f4 v[138:141], v[218:225], v[26:33], v[138:141], v188, v188 op_sel_hi:[0,0,0]
	v_mfma_scale_f32_16x16x128_f8f6f4 v[130:133], v[226:233], v[26:33], v[130:133], v188, v188 op_sel_hi:[0,0,0]
	v_mfma_scale_f32_16x16x128_f8f6f4 v[122:125], v[218:225], v[202:209], v[122:125], v188, v188 op_sel_hi:[0,0,0]
	v_mfma_scale_f32_16x16x128_f8f6f4 v[114:117], v[226:233], v[202:209], v[114:117], v188, v188 op_sel_hi:[0,0,0]
	v_mfma_scale_f32_16x16x128_f8f6f4 v[106:109], v[218:225], v[210:217], v[106:109], v188, v188 op_sel_hi:[0,0,0]
	v_mfma_scale_f32_16x16x128_f8f6f4 v[98:101], v[226:233], v[210:217], v[98:101], v188, v188 op_sel_hi:[0,0,0]
	s_mov_b32 m0, s51
	v_lshl_add_u64 v[180:181], v[186:187], 0, s[24:25]
	s_barrier
	ds_read_b128 v[18:21], v169 offset:49152
	ds_read_b128 v[22:25], v169 offset:50176
	ds_read_b128 v[26:29], v169 offset:51200
	ds_read_b128 v[30:33], v169 offset:52224
	ds_read_b128 v[202:205], v169 offset:53248
	ds_read_b128 v[206:209], v169 offset:54272
	ds_read_b128 v[210:213], v169 offset:55296
	ds_read_b128 v[214:217], v169 offset:56320
	global_load_lds_dwordx4 v[180:181], off
	v_lshl_add_u64 v[180:181], v[184:185], 0, s[24:25]
	s_mov_b32 m0, s52
	s_nop 0
	global_load_lds_dwordx4 v[180:181], off
	s_waitcnt vmcnt(10)
	s_barrier
	s_waitcnt lgkmcnt(0)
	s_waitcnt lgkmcnt(0)
	v_mfma_scale_f32_16x16x128_f8f6f4 v[94:97], v[2:9], v[18:25], v[94:97], v188, v188 op_sel_hi:[0,0,0]
	v_mfma_scale_f32_16x16x128_f8f6f4 v[86:89], v[10:17], v[18:25], v[86:89], v188, v188 op_sel_hi:[0,0,0]
	v_mfma_scale_f32_16x16x128_f8f6f4 v[78:81], v[2:9], v[26:33], v[78:81], v188, v188 op_sel_hi:[0,0,0]
	v_mfma_scale_f32_16x16x128_f8f6f4 v[70:73], v[10:17], v[26:33], v[70:73], v188, v188 op_sel_hi:[0,0,0]
	v_mfma_scale_f32_16x16x128_f8f6f4 v[62:65], v[2:9], v[202:209], v[62:65], v188, v188 op_sel_hi:[0,0,0]
	v_mfma_scale_f32_16x16x128_f8f6f4 v[54:57], v[10:17], v[202:209], v[54:57], v188, v188 op_sel_hi:[0,0,0]
	v_mfma_scale_f32_16x16x128_f8f6f4 v[46:49], v[2:9], v[210:217], v[46:49], v188, v188 op_sel_hi:[0,0,0]
	v_mfma_scale_f32_16x16x128_f8f6f4 v[38:41], v[10:17], v[210:217], v[38:41], v188, v188 op_sel_hi:[0,0,0]
	s_barrier
	s_add_u32 s0, s36, 0x20080
	s_addc_u32 s1, s37, 0
	s_add_i32 s36, s38, s43
	v_lshl_add_u64 v[2:3], s[0:1], 0, v[164:165]
	s_mov_b32 m0, s36
	s_nop 0
	global_load_lds_dwordx4 v[2:3], off
	v_lshl_add_u64 v[2:3], s[0:1], 0, v[166:167]
	s_add_i32 m0, s36, 0x2000
	s_nop 0
	global_load_lds_dwordx4 v[2:3], off
	s_waitcnt vmcnt(10)
	s_barrier
	v_mfma_scale_f32_16x16x128_f8f6f4 v[90:93], v[218:225], v[18:25], v[90:93], v188, v188 op_sel_hi:[0,0,0]
	v_mfma_scale_f32_16x16x128_f8f6f4 v[82:85], v[226:233], v[18:25], v[82:85], v188, v188 op_sel_hi:[0,0,0]
	v_mfma_scale_f32_16x16x128_f8f6f4 v[74:77], v[218:225], v[26:33], v[74:77], v188, v188 op_sel_hi:[0,0,0]
	v_mfma_scale_f32_16x16x128_f8f6f4 v[66:69], v[226:233], v[26:33], v[66:69], v188, v188 op_sel_hi:[0,0,0]
	v_mfma_scale_f32_16x16x128_f8f6f4 v[58:61], v[218:225], v[202:209], v[58:61], v188, v188 op_sel_hi:[0,0,0]
	v_mfma_scale_f32_16x16x128_f8f6f4 v[50:53], v[226:233], v[202:209], v[50:53], v188, v188 op_sel_hi:[0,0,0]
	v_mfma_scale_f32_16x16x128_f8f6f4 v[42:45], v[218:225], v[210:217], v[42:45], v188, v188 op_sel_hi:[0,0,0]
	v_mfma_scale_f32_16x16x128_f8f6f4 v[34:37], v[226:233], v[210:217], v[34:37], v188, v188 op_sel_hi:[0,0,0]
	s_add_i32 s56, s56, 2
	s_cmp_gt_u32 s56, 5
	s_mov_b64 s[38:39], s[14:15]
	s_barrier
	s_cbranch_scc0 .LBB0_2041
	v_mul_f32_e32 v5, 0x3c800000, v158
	v_mul_f32_e32 v6, 0xbfb8aa3b, v5
	v_exp_f32_e32 v6, v6
	s_ashr_i32 s35, s34, 31
	s_ashr_i32 s31, s30, 31
	s_lshl_b64 s[14:15], s[34:35], 18
	v_add_f32_e32 v6, 1.0, v6
	v_rcp_f32_e32 v6, v6
	s_lshl_b64 s[30:31], s[30:31], 15
	v_mov_b32_e32 v3, v195
	s_add_u32 s0, s6, s14
	v_mul_f32_e32 v5, v5, v6
	v_mul_f32_e32 v6, 0x3c800000, v159
	v_mul_f32_e32 v7, 0xbfb8aa3b, v6
	v_exp_f32_e32 v7, v7
	v_mul_f32_e32 v5, v5, v154
	v_mul_f32_e32 v5, 0x3e000000, v5
	v_med3_f32 v5, v5, s10, v190
	v_add_f32_e32 v7, 1.0, v7
	v_rcp_f32_e32 v7, v7
	s_nop 15
	s_nop 15
	v_mov_b32_e32 v2, v196
	v_mul_f32_e32 v6, v6, v7
	v_mul_f32_e32 v7, 0x3c800000, v160
	v_mul_f32_e32 v8, 0xbfb8aa3b, v7
	v_exp_f32_e32 v8, v8
	v_mul_f32_e32 v6, v6, v155
	v_mul_f32_e32 v6, 0x3e000000, v6
	v_add_u32_e32 v4, s49, v3
	v_add_f32_e32 v8, 1.0, v8
	v_rcp_f32_e32 v8, v8
	s_addc_u32 s1, s7, s15
	s_add_u32 s14, s0, s30
	v_mul_f32_e32 v7, v7, v8
	v_mul_f32_e32 v8, 0x3c800000, v161
	v_mul_f32_e32 v9, 0xbfb8aa3b, v8
	v_exp_f32_e32 v9, v9
	v_mul_f32_e32 v7, v7, v156
	v_mul_f32_e32 v7, 0x3e000000, v7
	v_lshl_add_u32 v2, v2, 3, s50
	v_add_f32_e32 v9, 1.0, v9
	v_rcp_f32_e32 v9, v9
	s_addc_u32 s15, s1, s31
	v_ashrrev_i32_e32 v3, 31, v2
	s_and_b64 vcc, exec, s[12:13]
	v_mul_f32_e32 v8, v8, v9
	v_mul_f32_e32 v9, 0x3c800000, v150
	v_mul_f32_e32 v10, 0xbfb8aa3b, v9
	v_exp_f32_e32 v10, v10
	v_mul_f32_e32 v8, v8, v157
	v_mul_f32_e32 v8, 0x3e000000, v8
	v_mov_b32_e32 v174, v200
	v_add_f32_e32 v10, 1.0, v10
	v_rcp_f32_e32 v10, v10
	v_mov_b32_e32 v172, v199
	v_mov_b32_e32 v170, v198
	v_mov_b32_e32 v168, v171
	v_mul_f32_e32 v9, v9, v10
	v_mul_f32_e32 v10, 0x3c800000, v151
	v_mul_f32_e32 v11, 0xbfb8aa3b, v10
	v_exp_f32_e32 v11, v11
	v_mul_f32_e32 v9, v9, v146
	v_mul_f32_e32 v9, 0x3e000000, v9
	s_mov_b32 s30, s28
	v_add_f32_e32 v11, 1.0, v11
	v_rcp_f32_e32 v11, v11
	s_mov_b32 s34, s54
	s_mov_b64 s[36:37], s[16:17]
	v_mul_f32_e32 v10, v10, v11
	v_mul_f32_e32 v11, 0x3c800000, v152
	v_mul_f32_e32 v12, 0xbfb8aa3b, v11
	v_exp_f32_e32 v12, v12
	v_mul_f32_e32 v10, v10, v147
	v_mul_f32_e32 v10, 0x3e000000, v10
	v_add_f32_e32 v12, 1.0, v12
	v_rcp_f32_e32 v12, v12
	s_nop 0
	v_mul_f32_e32 v11, v11, v12
	v_mul_f32_e32 v12, 0x3c800000, v153
	v_mul_f32_e32 v13, 0xbfb8aa3b, v12
	v_exp_f32_e32 v13, v13
	v_mul_f32_e32 v11, v11, v148
	v_mul_f32_e32 v11, 0x3e000000, v11
	v_add_f32_e32 v13, 1.0, v13
	v_rcp_f32_e32 v13, v13
	s_nop 0
	v_mul_f32_e32 v12, v12, v13
	v_med3_f32 v13, v6, s10, v190
	v_mov_b32_e32 v6, v163
	v_cvt_pk_fp8_f32 v6, v5, v13
	v_med3_f32 v5, v7, s10, v190
	v_med3_f32 v7, v8, s10, v190
	v_med3_f32 v8, v10, s10, v190
	v_cvt_pk_fp8_f32 v6, v5, v7 op_sel:[0,0,1]
	v_med3_f32 v5, v9, s10, v190
	v_mov_b32_e32 v7, v163
	v_cvt_pk_fp8_f32 v7, v5, v8
	v_mul_f32_e32 v12, v12, v149
	v_mul_f32_e32 v12, 0x3e000000, v12
	v_med3_f32 v5, v11, s10, v190
	v_med3_f32 v8, v12, s10, v190
	v_cvt_pk_fp8_f32 v7, v5, v8 op_sel:[0,0,1]
	v_ashrrev_i32_e32 v5, 31, v4
	v_lshlrev_b64 v[8:9], 7, v[4:5]
	v_lshl_add_u64 v[8:9], s[14:15], 0, v[8:9]
	v_lshl_add_u64 v[8:9], v[8:9], 0, v[2:3]
	v_mul_f32_e32 v5, 0x3c800000, v142
	global_store_dwordx2 v[8:9], v[6:7], off
	v_mul_f32_e32 v6, 0xbfb8aa3b, v5
	v_exp_f32_e32 v6, v6
	s_nop 0
	v_add_f32_e32 v6, 1.0, v6
	v_rcp_f32_e32 v6, v6
	s_nop 0
	v_mul_f32_e32 v5, v5, v6
	v_mul_f32_e32 v6, 0x3c800000, v143
	v_mul_f32_e32 v7, 0xbfb8aa3b, v6
	v_exp_f32_e32 v7, v7
	v_mul_f32_e32 v5, v5, v138
	v_mul_f32_e32 v5, 0x3e000000, v5
	v_med3_f32 v5, v5, s10, v190
	v_add_f32_e32 v7, 1.0, v7
	v_rcp_f32_e32 v7, v7
	s_nop 0
	v_mul_f32_e32 v6, v6, v7
	v_mul_f32_e32 v6, v6, v139
	v_mul_f32_e32 v7, 0x3e000000, v6
	v_mul_f32_e32 v6, 0x3c800000, v144
	v_mul_f32_e32 v8, 0xbfb8aa3b, v6
	v_exp_f32_e32 v8, v8
	v_med3_f32 v7, v7, s10, v190
	v_add_f32_e32 v8, 1.0, v8
	v_rcp_f32_e32 v8, v8
	s_nop 0
	v_mul_f32_e32 v6, v6, v8
	v_mul_f32_e32 v6, v6, v140
	v_mul_f32_e32 v9, 0x3e000000, v6
	v_mul_f32_e32 v6, 0x3c800000, v145
	v_mul_f32_e32 v8, 0xbfb8aa3b, v6
	v_exp_f32_e32 v8, v8
	s_nop 0
	v_add_f32_e32 v8, 1.0, v8
	v_rcp_f32_e32 v8, v8
	s_nop 0
	v_mul_f32_e32 v6, v6, v8
	v_mul_f32_e32 v6, v6, v141
	v_mul_f32_e32 v10, 0x3e000000, v6
	v_mul_f32_e32 v6, 0x3c800000, v134
	v_mul_f32_e32 v8, 0xbfb8aa3b, v6
	v_exp_f32_e32 v8, v8
	s_nop 0
	v_add_f32_e32 v8, 1.0, v8
	v_rcp_f32_e32 v8, v8
	s_nop 0
	v_mul_f32_e32 v6, v6, v8
	v_mul_f32_e32 v6, v6, v130
	v_mul_f32_e32 v11, 0x3e000000, v6
	v_mul_f32_e32 v6, 0x3c800000, v135
	v_mul_f32_e32 v8, 0xbfb8aa3b, v6
	v_exp_f32_e32 v8, v8
	s_nop 0
	v_add_f32_e32 v8, 1.0, v8
	v_rcp_f32_e32 v8, v8
	s_nop 0
	v_mul_f32_e32 v6, v6, v8
	v_mul_f32_e32 v6, v6, v131
	v_mul_f32_e32 v12, 0x3e000000, v6
	v_mul_f32_e32 v6, 0x3c800000, v136
	v_mul_f32_e32 v8, 0xbfb8aa3b, v6
	v_exp_f32_e32 v8, v8
	s_nop 0
	v_add_f32_e32 v8, 1.0, v8
	v_rcp_f32_e32 v8, v8
	s_nop 0
	v_mul_f32_e32 v6, v6, v8
	v_mul_f32_e32 v6, v6, v132
	v_mul_f32_e32 v13, 0x3e000000, v6
	v_mul_f32_e32 v6, 0x3c800000, v137
	v_mul_f32_e32 v8, 0xbfb8aa3b, v6
	v_exp_f32_e32 v8, v8
	s_nop 0
	v_add_f32_e32 v8, 1.0, v8
	v_rcp_f32_e32 v8, v8
	s_nop 0
	v_mul_f32_e32 v6, v6, v8
	v_mov_b32_e32 v8, v163
	v_cvt_pk_fp8_f32 v8, v5, v7
	v_med3_f32 v5, v9, s10, v190
	v_med3_f32 v7, v10, s10, v190
	v_mov_b32_e32 v9, v163
	v_cvt_pk_fp8_f32 v8, v5, v7 op_sel:[0,0,1]
	v_med3_f32 v5, v11, s10, v190
	v_med3_f32 v7, v12, s10, v190
	v_cvt_pk_fp8_f32 v9, v5, v7
	v_mul_f32_e32 v6, v6, v133
	v_mul_f32_e32 v14, 0x3e000000, v6
	v_add_u32_e32 v6, 16, v4
	v_med3_f32 v5, v13, s10, v190
	v_med3_f32 v7, v14, s10, v190
	v_cvt_pk_fp8_f32 v9, v5, v7 op_sel:[0,0,1]
	v_ashrrev_i32_e32 v7, 31, v6
	v_lshlrev_b64 v[6:7], 7, v[6:7]
	v_lshl_add_u64 v[6:7], s[14:15], 0, v[6:7]
	v_lshl_add_u64 v[6:7], v[6:7], 0, v[2:3]
	v_mul_f32_e32 v5, 0x3c800000, v126
	global_store_dwordx2 v[6:7], v[8:9], off
	v_mul_f32_e32 v6, 0xbfb8aa3b, v5
	v_exp_f32_e32 v6, v6
	s_nop 0
	v_add_f32_e32 v6, 1.0, v6
	v_rcp_f32_e32 v6, v6
	s_nop 0
	v_mul_f32_e32 v5, v5, v6
	v_mul_f32_e32 v6, 0x3c800000, v127
	v_mul_f32_e32 v7, 0xbfb8aa3b, v6
	v_exp_f32_e32 v7, v7
	v_mul_f32_e32 v5, v5, v122
	v_mul_f32_e32 v5, 0x3e000000, v5
	v_med3_f32 v5, v5, s10, v190
	v_add_f32_e32 v7, 1.0, v7
	v_rcp_f32_e32 v7, v7
	s_nop 0
	v_mul_f32_e32 v6, v6, v7
	v_mul_f32_e32 v6, v6, v123
	v_mul_f32_e32 v7, 0x3e000000, v6
	v_mul_f32_e32 v6, 0x3c800000, v128
	v_mul_f32_e32 v8, 0xbfb8aa3b, v6
	v_exp_f32_e32 v8, v8
	v_med3_f32 v7, v7, s10, v190
	v_add_f32_e32 v8, 1.0, v8
	v_rcp_f32_e32 v8, v8
	s_nop 0
	v_mul_f32_e32 v6, v6, v8
	v_mul_f32_e32 v6, v6, v124
	v_mul_f32_e32 v9, 0x3e000000, v6
	v_mul_f32_e32 v6, 0x3c800000, v129
	v_mul_f32_e32 v8, 0xbfb8aa3b, v6
	v_exp_f32_e32 v8, v8
	s_nop 0
	v_add_f32_e32 v8, 1.0, v8
	v_rcp_f32_e32 v8, v8
	s_nop 0
	v_mul_f32_e32 v6, v6, v8
	v_mul_f32_e32 v6, v6, v125
	v_mul_f32_e32 v10, 0x3e000000, v6
	v_mul_f32_e32 v6, 0x3c800000, v118
	v_mul_f32_e32 v8, 0xbfb8aa3b, v6
	v_exp_f32_e32 v8, v8
	s_nop 0
	v_add_f32_e32 v8, 1.0, v8
	v_rcp_f32_e32 v8, v8
	s_nop 0
	v_mul_f32_e32 v6, v6, v8
	v_mul_f32_e32 v6, v6, v114
	v_mul_f32_e32 v11, 0x3e000000, v6
	v_mul_f32_e32 v6, 0x3c800000, v119
	v_mul_f32_e32 v8, 0xbfb8aa3b, v6
	v_exp_f32_e32 v8, v8
	s_nop 0
	v_add_f32_e32 v8, 1.0, v8
	v_rcp_f32_e32 v8, v8
	s_nop 0
	v_mul_f32_e32 v6, v6, v8
	v_mul_f32_e32 v6, v6, v115
	v_mul_f32_e32 v12, 0x3e000000, v6
	v_mul_f32_e32 v6, 0x3c800000, v120
	v_mul_f32_e32 v8, 0xbfb8aa3b, v6
	v_exp_f32_e32 v8, v8
	s_nop 0
	v_add_f32_e32 v8, 1.0, v8
	v_rcp_f32_e32 v8, v8
	s_nop 0
	v_mul_f32_e32 v6, v6, v8
	v_mul_f32_e32 v6, v6, v116
	v_mul_f32_e32 v13, 0x3e000000, v6
	v_mul_f32_e32 v6, 0x3c800000, v121
	v_mul_f32_e32 v8, 0xbfb8aa3b, v6
	v_exp_f32_e32 v8, v8
	s_nop 0
	v_add_f32_e32 v8, 1.0, v8
	v_rcp_f32_e32 v8, v8
	s_nop 0
	v_mul_f32_e32 v6, v6, v8
	v_mov_b32_e32 v8, v163
	v_cvt_pk_fp8_f32 v8, v5, v7
	v_med3_f32 v5, v9, s10, v190
	v_med3_f32 v7, v10, s10, v190
	v_mov_b32_e32 v9, v163
	v_cvt_pk_fp8_f32 v8, v5, v7 op_sel:[0,0,1]
	v_med3_f32 v5, v11, s10, v190
	v_med3_f32 v7, v12, s10, v190
	v_cvt_pk_fp8_f32 v9, v5, v7
	v_mul_f32_e32 v6, v6, v117
	v_mul_f32_e32 v14, 0x3e000000, v6
	v_add_u32_e32 v6, 32, v4
	v_med3_f32 v5, v13, s10, v190
	v_med3_f32 v7, v14, s10, v190
	v_cvt_pk_fp8_f32 v9, v5, v7 op_sel:[0,0,1]
	v_ashrrev_i32_e32 v7, 31, v6
	v_lshlrev_b64 v[6:7], 7, v[6:7]
	v_lshl_add_u64 v[6:7], s[14:15], 0, v[6:7]
	v_lshl_add_u64 v[6:7], v[6:7], 0, v[2:3]
	v_mul_f32_e32 v5, 0x3c800000, v110
	global_store_dwordx2 v[6:7], v[8:9], off
	v_mul_f32_e32 v6, 0xbfb8aa3b, v5
	v_exp_f32_e32 v6, v6
	s_nop 0
	v_add_f32_e32 v6, 1.0, v6
	v_rcp_f32_e32 v6, v6
	s_nop 0
	v_mul_f32_e32 v5, v5, v6
	v_mul_f32_e32 v6, 0x3c800000, v111
	v_mul_f32_e32 v7, 0xbfb8aa3b, v6
	v_exp_f32_e32 v7, v7
	v_mul_f32_e32 v5, v5, v106
	v_mul_f32_e32 v5, 0x3e000000, v5
	v_med3_f32 v5, v5, s10, v190
	v_add_f32_e32 v7, 1.0, v7
	v_rcp_f32_e32 v7, v7
	s_nop 0
	v_mul_f32_e32 v6, v6, v7
	v_mul_f32_e32 v6, v6, v107
	v_mul_f32_e32 v7, 0x3e000000, v6
	v_mul_f32_e32 v6, 0x3c800000, v112
	v_mul_f32_e32 v8, 0xbfb8aa3b, v6
	v_exp_f32_e32 v8, v8
	v_med3_f32 v7, v7, s10, v190
	v_add_f32_e32 v8, 1.0, v8
	v_rcp_f32_e32 v8, v8
	s_nop 0
	v_mul_f32_e32 v6, v6, v8
	v_mul_f32_e32 v6, v6, v108
	v_mul_f32_e32 v9, 0x3e000000, v6
	v_mul_f32_e32 v6, 0x3c800000, v113
	v_mul_f32_e32 v8, 0xbfb8aa3b, v6
	v_exp_f32_e32 v8, v8
	s_nop 0
	v_add_f32_e32 v8, 1.0, v8
	v_rcp_f32_e32 v8, v8
	s_nop 0
	v_mul_f32_e32 v6, v6, v8
	v_mul_f32_e32 v6, v6, v109
	v_mul_f32_e32 v10, 0x3e000000, v6
	v_mul_f32_e32 v6, 0x3c800000, v102
	v_mul_f32_e32 v8, 0xbfb8aa3b, v6
	v_exp_f32_e32 v8, v8
	s_nop 0
	v_add_f32_e32 v8, 1.0, v8
	v_rcp_f32_e32 v8, v8
	s_nop 0
	v_mul_f32_e32 v6, v6, v8
	v_mul_f32_e32 v6, v6, v98
	v_mul_f32_e32 v11, 0x3e000000, v6
	v_mul_f32_e32 v6, 0x3c800000, v103
	v_mul_f32_e32 v8, 0xbfb8aa3b, v6
	v_exp_f32_e32 v8, v8
	s_nop 0
	v_add_f32_e32 v8, 1.0, v8
	v_rcp_f32_e32 v8, v8
	s_nop 0
	v_mul_f32_e32 v6, v6, v8
	v_mul_f32_e32 v6, v6, v99
	v_mul_f32_e32 v12, 0x3e000000, v6
	v_mul_f32_e32 v6, 0x3c800000, v104
	v_mul_f32_e32 v8, 0xbfb8aa3b, v6
	v_exp_f32_e32 v8, v8
	s_nop 0
	v_add_f32_e32 v8, 1.0, v8
	v_rcp_f32_e32 v8, v8
	s_nop 0
	v_mul_f32_e32 v6, v6, v8
	v_mul_f32_e32 v6, v6, v100
	v_mul_f32_e32 v13, 0x3e000000, v6
	v_mul_f32_e32 v6, 0x3c800000, v105
	v_mul_f32_e32 v8, 0xbfb8aa3b, v6
	v_exp_f32_e32 v8, v8
	s_nop 0
	v_add_f32_e32 v8, 1.0, v8
	v_rcp_f32_e32 v8, v8
	s_nop 0
	v_mul_f32_e32 v6, v6, v8
	v_mov_b32_e32 v8, v163
	v_cvt_pk_fp8_f32 v8, v5, v7
	v_med3_f32 v5, v9, s10, v190
	v_med3_f32 v7, v10, s10, v190
	v_mov_b32_e32 v9, v163
	v_cvt_pk_fp8_f32 v8, v5, v7 op_sel:[0,0,1]
	v_med3_f32 v5, v11, s10, v190
	v_med3_f32 v7, v12, s10, v190
	v_cvt_pk_fp8_f32 v9, v5, v7
	v_mul_f32_e32 v6, v6, v101
	v_mul_f32_e32 v14, 0x3e000000, v6
	v_add_u32_e32 v6, 48, v4
	v_med3_f32 v5, v13, s10, v190
	v_med3_f32 v7, v14, s10, v190
	v_cvt_pk_fp8_f32 v9, v5, v7 op_sel:[0,0,1]
	v_ashrrev_i32_e32 v7, 31, v6
	v_lshlrev_b64 v[6:7], 7, v[6:7]
	v_lshl_add_u64 v[6:7], s[14:15], 0, v[6:7]
	v_lshl_add_u64 v[6:7], v[6:7], 0, v[2:3]
	v_mul_f32_e32 v5, 0x3c800000, v94
	global_store_dwordx2 v[6:7], v[8:9], off
	v_mul_f32_e32 v7, 0xbfb8aa3b, v5
	v_exp_f32_e32 v7, v7
	v_add_u32_e32 v6, 0x80, v4
	v_add_f32_e32 v7, 1.0, v7
	v_rcp_f32_e32 v7, v7
	s_nop 0
	v_mul_f32_e32 v5, v5, v7
	v_mul_f32_e32 v7, 0x3c800000, v95
	v_mul_f32_e32 v8, 0xbfb8aa3b, v7
	v_exp_f32_e32 v8, v8
	v_mul_f32_e32 v5, v5, v90
	v_mul_f32_e32 v5, 0x3e000000, v5
	v_med3_f32 v5, v5, s10, v190
	v_add_f32_e32 v8, 1.0, v8
	v_rcp_f32_e32 v8, v8
	s_nop 0
	v_mul_f32_e32 v7, v7, v8
	v_mul_f32_e32 v8, 0x3c800000, v96
	v_mul_f32_e32 v9, 0xbfb8aa3b, v8
	v_exp_f32_e32 v9, v9
	v_mul_f32_e32 v7, v7, v91
	v_mul_f32_e32 v7, 0x3e000000, v7
	v_med3_f32 v7, v7, s10, v190
	v_add_f32_e32 v9, 1.0, v9
	v_rcp_f32_e32 v9, v9
	s_nop 0
	v_mul_f32_e32 v8, v8, v9
	v_mul_f32_e32 v8, v8, v92
	v_mul_f32_e32 v9, 0x3e000000, v8
	v_mul_f32_e32 v8, 0x3c800000, v97
	v_mul_f32_e32 v10, 0xbfb8aa3b, v8
	v_exp_f32_e32 v10, v10
	s_nop 0
	v_add_f32_e32 v10, 1.0, v10
	v_rcp_f32_e32 v10, v10
	s_nop 0
	v_mul_f32_e32 v8, v8, v10
	v_mul_f32_e32 v8, v8, v93
	v_mul_f32_e32 v10, 0x3e000000, v8
	v_mul_f32_e32 v8, 0x3c800000, v86
	v_mul_f32_e32 v11, 0xbfb8aa3b, v8
	v_exp_f32_e32 v11, v11
	s_nop 0
	v_add_f32_e32 v11, 1.0, v11
	v_rcp_f32_e32 v11, v11
	s_nop 0
	v_mul_f32_e32 v8, v8, v11
	v_mul_f32_e32 v8, v8, v82
	v_mul_f32_e32 v11, 0x3e000000, v8
	v_mul_f32_e32 v8, 0x3c800000, v87
	v_mul_f32_e32 v12, 0xbfb8aa3b, v8
	v_exp_f32_e32 v12, v12
	s_nop 0
	v_add_f32_e32 v12, 1.0, v12
	v_rcp_f32_e32 v12, v12
	s_nop 0
	v_mul_f32_e32 v8, v8, v12
	v_mul_f32_e32 v8, v8, v83
	v_mul_f32_e32 v12, 0x3e000000, v8
	v_mul_f32_e32 v8, 0x3c800000, v88
	v_mul_f32_e32 v13, 0xbfb8aa3b, v8
	v_exp_f32_e32 v13, v13
	s_nop 0
	v_add_f32_e32 v13, 1.0, v13
	v_rcp_f32_e32 v13, v13
	s_nop 0
	v_mul_f32_e32 v8, v8, v13
	v_mul_f32_e32 v8, v8, v84
	v_mul_f32_e32 v13, 0x3e000000, v8
	v_mul_f32_e32 v8, 0x3c800000, v89
	v_mul_f32_e32 v14, 0xbfb8aa3b, v8
	v_exp_f32_e32 v14, v14
	s_nop 0
	v_add_f32_e32 v14, 1.0, v14
	v_rcp_f32_e32 v14, v14
	s_nop 0
	v_mul_f32_e32 v8, v8, v14
	v_mul_f32_e32 v8, v8, v85
	v_mul_f32_e32 v14, 0x3e000000, v8
	v_mov_b32_e32 v8, v163
	v_cvt_pk_fp8_f32 v8, v5, v7
	v_med3_f32 v5, v9, s10, v190
	v_med3_f32 v7, v10, s10, v190
	v_mov_b32_e32 v9, v163
	v_cvt_pk_fp8_f32 v8, v5, v7 op_sel:[0,0,1]
	v_med3_f32 v5, v11, s10, v190
	v_med3_f32 v7, v12, s10, v190
	v_cvt_pk_fp8_f32 v9, v5, v7
	v_med3_f32 v5, v13, s10, v190
	v_med3_f32 v7, v14, s10, v190
	v_cvt_pk_fp8_f32 v9, v5, v7 op_sel:[0,0,1]
	v_ashrrev_i32_e32 v7, 31, v6
	v_lshlrev_b64 v[6:7], 7, v[6:7]
	v_lshl_add_u64 v[6:7], s[14:15], 0, v[6:7]
	v_lshl_add_u64 v[6:7], v[6:7], 0, v[2:3]
	v_mul_f32_e32 v5, 0x3c800000, v78
	global_store_dwordx2 v[6:7], v[8:9], off
	v_mul_f32_e32 v6, 0xbfb8aa3b, v5
	v_exp_f32_e32 v6, v6
	s_nop 0
	v_add_f32_e32 v6, 1.0, v6
	v_rcp_f32_e32 v6, v6
	s_nop 0
	v_mul_f32_e32 v5, v5, v6
	v_mul_f32_e32 v6, 0x3c800000, v79
	v_mul_f32_e32 v7, 0xbfb8aa3b, v6
	v_exp_f32_e32 v7, v7
	v_mul_f32_e32 v5, v5, v74
	v_mul_f32_e32 v5, 0x3e000000, v5
	v_med3_f32 v5, v5, s10, v190
	v_add_f32_e32 v7, 1.0, v7
	v_rcp_f32_e32 v7, v7
	s_nop 0
	v_mul_f32_e32 v6, v6, v7
	v_mul_f32_e32 v6, v6, v75
	v_mul_f32_e32 v7, 0x3e000000, v6
	v_mul_f32_e32 v6, 0x3c800000, v80
	v_mul_f32_e32 v8, 0xbfb8aa3b, v6
	v_exp_f32_e32 v8, v8
	v_med3_f32 v7, v7, s10, v190
	v_add_f32_e32 v8, 1.0, v8
	v_rcp_f32_e32 v8, v8
	s_nop 0
	v_mul_f32_e32 v6, v6, v8
	v_mul_f32_e32 v6, v6, v76
	v_mul_f32_e32 v9, 0x3e000000, v6
	v_mul_f32_e32 v6, 0x3c800000, v81
	v_mul_f32_e32 v8, 0xbfb8aa3b, v6
	v_exp_f32_e32 v8, v8
	s_nop 0
	v_add_f32_e32 v8, 1.0, v8
	v_rcp_f32_e32 v8, v8
	s_nop 0
	v_mul_f32_e32 v6, v6, v8
	v_mul_f32_e32 v6, v6, v77
	v_mul_f32_e32 v10, 0x3e000000, v6
	v_mul_f32_e32 v6, 0x3c800000, v70
	v_mul_f32_e32 v8, 0xbfb8aa3b, v6
	v_exp_f32_e32 v8, v8
	s_nop 0
	v_add_f32_e32 v8, 1.0, v8
	v_rcp_f32_e32 v8, v8
	s_nop 0
	v_mul_f32_e32 v6, v6, v8
	v_mul_f32_e32 v6, v6, v66
	v_mul_f32_e32 v11, 0x3e000000, v6
	v_mul_f32_e32 v6, 0x3c800000, v71
	v_mul_f32_e32 v8, 0xbfb8aa3b, v6
	v_exp_f32_e32 v8, v8
	s_nop 0
	v_add_f32_e32 v8, 1.0, v8
	v_rcp_f32_e32 v8, v8
	s_nop 0
	v_mul_f32_e32 v6, v6, v8
	v_mul_f32_e32 v6, v6, v67
	v_mul_f32_e32 v12, 0x3e000000, v6
	v_mul_f32_e32 v6, 0x3c800000, v72
	v_mul_f32_e32 v8, 0xbfb8aa3b, v6
	v_exp_f32_e32 v8, v8
	s_nop 0
	v_add_f32_e32 v8, 1.0, v8
	v_rcp_f32_e32 v8, v8
	s_nop 0
	v_mul_f32_e32 v6, v6, v8
	v_mul_f32_e32 v6, v6, v68
	v_mul_f32_e32 v13, 0x3e000000, v6
	v_mul_f32_e32 v6, 0x3c800000, v73
	v_mul_f32_e32 v8, 0xbfb8aa3b, v6
	v_exp_f32_e32 v8, v8
	s_nop 0
	v_add_f32_e32 v8, 1.0, v8
	v_rcp_f32_e32 v8, v8
	s_nop 0
	v_mul_f32_e32 v6, v6, v8
	v_mov_b32_e32 v8, v163
	v_cvt_pk_fp8_f32 v8, v5, v7
	v_med3_f32 v5, v9, s10, v190
	v_med3_f32 v7, v10, s10, v190
	v_mov_b32_e32 v9, v163
	v_cvt_pk_fp8_f32 v8, v5, v7 op_sel:[0,0,1]
	v_med3_f32 v5, v11, s10, v190
	v_med3_f32 v7, v12, s10, v190
	v_cvt_pk_fp8_f32 v9, v5, v7
	v_mul_f32_e32 v6, v6, v69
	v_mul_f32_e32 v14, 0x3e000000, v6
	v_add_u32_e32 v6, 0x90, v4
	v_med3_f32 v5, v13, s10, v190
	v_med3_f32 v7, v14, s10, v190
	v_cvt_pk_fp8_f32 v9, v5, v7 op_sel:[0,0,1]
	v_ashrrev_i32_e32 v7, 31, v6
	v_lshlrev_b64 v[6:7], 7, v[6:7]
	v_lshl_add_u64 v[6:7], s[14:15], 0, v[6:7]
	v_lshl_add_u64 v[6:7], v[6:7], 0, v[2:3]
	v_mul_f32_e32 v5, 0x3c800000, v62
	global_store_dwordx2 v[6:7], v[8:9], off
	v_mul_f32_e32 v6, 0xbfb8aa3b, v5
	v_exp_f32_e32 v6, v6
	s_nop 0
	v_add_f32_e32 v6, 1.0, v6
	v_rcp_f32_e32 v6, v6
	s_nop 0
	v_mul_f32_e32 v5, v5, v6
	v_mul_f32_e32 v6, 0x3c800000, v63
	v_mul_f32_e32 v7, 0xbfb8aa3b, v6
	v_exp_f32_e32 v7, v7
	v_mul_f32_e32 v5, v5, v58
	v_mul_f32_e32 v5, 0x3e000000, v5
	v_med3_f32 v5, v5, s10, v190
	v_add_f32_e32 v7, 1.0, v7
	v_rcp_f32_e32 v7, v7
	s_nop 0
	v_mul_f32_e32 v6, v6, v7
	v_mul_f32_e32 v6, v6, v59
	v_mul_f32_e32 v7, 0x3e000000, v6
	v_mul_f32_e32 v6, 0x3c800000, v64
	v_mul_f32_e32 v8, 0xbfb8aa3b, v6
	v_exp_f32_e32 v8, v8
	v_med3_f32 v7, v7, s10, v190
	v_add_f32_e32 v8, 1.0, v8
	v_rcp_f32_e32 v8, v8
	s_nop 0
	v_mul_f32_e32 v6, v6, v8
	v_mul_f32_e32 v6, v6, v60
	v_mul_f32_e32 v9, 0x3e000000, v6
	v_mul_f32_e32 v6, 0x3c800000, v65
	v_mul_f32_e32 v8, 0xbfb8aa3b, v6
	v_exp_f32_e32 v8, v8
	s_nop 0
	v_add_f32_e32 v8, 1.0, v8
	v_rcp_f32_e32 v8, v8
	s_nop 0
	v_mul_f32_e32 v6, v6, v8
	v_mul_f32_e32 v6, v6, v61
	v_mul_f32_e32 v10, 0x3e000000, v6
	v_mul_f32_e32 v6, 0x3c800000, v54
	v_mul_f32_e32 v8, 0xbfb8aa3b, v6
	v_exp_f32_e32 v8, v8
	s_nop 0
	v_add_f32_e32 v8, 1.0, v8
	v_rcp_f32_e32 v8, v8
	s_nop 0
	v_mul_f32_e32 v6, v6, v8
	v_mul_f32_e32 v6, v6, v50
	v_mul_f32_e32 v11, 0x3e000000, v6
	v_mul_f32_e32 v6, 0x3c800000, v55
	v_mul_f32_e32 v8, 0xbfb8aa3b, v6
	v_exp_f32_e32 v8, v8
	s_nop 0
	v_add_f32_e32 v8, 1.0, v8
	v_rcp_f32_e32 v8, v8
	s_nop 0
	v_mul_f32_e32 v6, v6, v8
	v_mul_f32_e32 v6, v6, v51
	v_mul_f32_e32 v12, 0x3e000000, v6
	v_mul_f32_e32 v6, 0x3c800000, v56
	v_mul_f32_e32 v8, 0xbfb8aa3b, v6
	v_exp_f32_e32 v8, v8
	s_nop 0
	v_add_f32_e32 v8, 1.0, v8
	v_rcp_f32_e32 v8, v8
	s_nop 0
	v_mul_f32_e32 v6, v6, v8
	v_mul_f32_e32 v6, v6, v52
	v_mul_f32_e32 v13, 0x3e000000, v6
	v_mul_f32_e32 v6, 0x3c800000, v57
	v_mul_f32_e32 v8, 0xbfb8aa3b, v6
	v_exp_f32_e32 v8, v8
	s_nop 0
	v_add_f32_e32 v8, 1.0, v8
	v_rcp_f32_e32 v8, v8
	s_nop 0
	v_mul_f32_e32 v6, v6, v8
	v_mov_b32_e32 v8, v163
	v_cvt_pk_fp8_f32 v8, v5, v7
	v_med3_f32 v5, v9, s10, v190
	v_med3_f32 v7, v10, s10, v190
	v_mov_b32_e32 v9, v163
	v_cvt_pk_fp8_f32 v8, v5, v7 op_sel:[0,0,1]
	v_med3_f32 v5, v11, s10, v190
	v_med3_f32 v7, v12, s10, v190
	v_cvt_pk_fp8_f32 v9, v5, v7
	v_mul_f32_e32 v6, v6, v53
	v_mul_f32_e32 v14, 0x3e000000, v6
	v_add_u32_e32 v6, 0xa0, v4
	v_med3_f32 v5, v13, s10, v190
	v_med3_f32 v7, v14, s10, v190
	v_cvt_pk_fp8_f32 v9, v5, v7 op_sel:[0,0,1]
	v_ashrrev_i32_e32 v7, 31, v6
	v_lshlrev_b64 v[6:7], 7, v[6:7]
	v_lshl_add_u64 v[6:7], s[14:15], 0, v[6:7]
	v_lshl_add_u64 v[6:7], v[6:7], 0, v[2:3]
	v_mul_f32_e32 v5, 0x3c800000, v46
	global_store_dwordx2 v[6:7], v[8:9], off
	v_mul_f32_e32 v6, 0xbfb8aa3b, v5
	v_exp_f32_e32 v6, v6
	v_add_u32_e32 v4, 0xb0, v4
	v_add_f32_e32 v6, 1.0, v6
	v_rcp_f32_e32 v6, v6
	s_nop 0
	v_mul_f32_e32 v5, v5, v6
	v_mul_f32_e32 v6, 0x3c800000, v47
	v_mul_f32_e32 v7, 0xbfb8aa3b, v6
	v_exp_f32_e32 v7, v7
	v_mul_f32_e32 v5, v5, v42
	v_mul_f32_e32 v5, 0x3e000000, v5
	v_med3_f32 v5, v5, s10, v190
	v_add_f32_e32 v7, 1.0, v7
	v_rcp_f32_e32 v7, v7
	s_nop 0
	v_mul_f32_e32 v6, v6, v7
	v_mul_f32_e32 v7, 0x3c800000, v48
	v_mul_f32_e32 v8, 0xbfb8aa3b, v7
	v_exp_f32_e32 v8, v8
	v_mul_f32_e32 v6, v6, v43
	v_mul_f32_e32 v6, 0x3e000000, v6
	v_add_f32_e32 v8, 1.0, v8
	v_rcp_f32_e32 v8, v8
	s_nop 0
	v_mul_f32_e32 v7, v7, v8
	v_mul_f32_e32 v8, 0x3c800000, v49
	v_mul_f32_e32 v9, 0xbfb8aa3b, v8
	v_exp_f32_e32 v9, v9
	v_mul_f32_e32 v7, v7, v44
	v_mul_f32_e32 v7, 0x3e000000, v7
	v_add_f32_e32 v9, 1.0, v9
	v_rcp_f32_e32 v9, v9
	s_nop 0
	v_mul_f32_e32 v8, v8, v9
	v_mul_f32_e32 v9, 0x3c800000, v38
	v_mul_f32_e32 v10, 0xbfb8aa3b, v9
	v_exp_f32_e32 v10, v10
	v_mul_f32_e32 v8, v8, v45
	v_mul_f32_e32 v8, 0x3e000000, v8
	v_add_f32_e32 v10, 1.0, v10
	v_rcp_f32_e32 v10, v10
	s_nop 0
	v_mul_f32_e32 v9, v9, v10
	v_mul_f32_e32 v10, 0x3c800000, v39
	v_mul_f32_e32 v11, 0xbfb8aa3b, v10
	v_exp_f32_e32 v11, v11
	v_mul_f32_e32 v9, v9, v34
	v_mul_f32_e32 v9, 0x3e000000, v9
	v_add_f32_e32 v11, 1.0, v11
	v_rcp_f32_e32 v11, v11
	s_nop 0
	v_mul_f32_e32 v10, v10, v11
	v_mul_f32_e32 v11, 0x3c800000, v40
	v_mul_f32_e32 v12, 0xbfb8aa3b, v11
	v_exp_f32_e32 v12, v12
	v_mul_f32_e32 v10, v10, v35
	v_mul_f32_e32 v10, 0x3e000000, v10
	v_add_f32_e32 v12, 1.0, v12
	v_rcp_f32_e32 v12, v12
	s_nop 0
	v_mul_f32_e32 v11, v11, v12
	v_mul_f32_e32 v12, 0x3c800000, v41
	v_mul_f32_e32 v13, 0xbfb8aa3b, v12
	v_exp_f32_e32 v13, v13
	v_mul_f32_e32 v11, v11, v36
	v_mul_f32_e32 v11, 0x3e000000, v11
	v_add_f32_e32 v13, 1.0, v13
	v_rcp_f32_e32 v13, v13
	s_nop 0
	v_mul_f32_e32 v12, v12, v13
	v_med3_f32 v13, v6, s10, v190
	v_mov_b32_e32 v6, v163
	v_cvt_pk_fp8_f32 v6, v5, v13
	v_med3_f32 v5, v7, s10, v190
	v_med3_f32 v7, v8, s10, v190
	v_med3_f32 v8, v10, s10, v190
	v_cvt_pk_fp8_f32 v6, v5, v7 op_sel:[0,0,1]
	v_med3_f32 v5, v9, s10, v190
	v_mov_b32_e32 v7, v163
	v_cvt_pk_fp8_f32 v7, v5, v8
	v_mul_f32_e32 v12, v12, v37
	v_mul_f32_e32 v12, 0x3e000000, v12
	v_med3_f32 v5, v11, s10, v190
	v_med3_f32 v8, v12, s10, v190
	v_cvt_pk_fp8_f32 v7, v5, v8 op_sel:[0,0,1]
	v_ashrrev_i32_e32 v5, 31, v4
	v_lshlrev_b64 v[4:5], 7, v[4:5]
	v_lshl_add_u64 v[4:5], s[14:15], 0, v[4:5]
	v_lshl_add_u64 v[2:3], v[4:5], 0, v[2:3]
	global_store_dwordx2 v[2:3], v[6:7], off
	s_cbranch_vccz .LBB0_2030
	s_waitcnt vmcnt(0)
	s_cmpk_gt_u32 s42, 0xff
	s_cbranch_scc1 .LBB0_1976
	s_barrier
	s_branch .LBB0_1976

.LBB0_2108:
	ds_read_b128 v[2:5], v169
	ds_read_b128 v[6:9], v169 offset:1024
	ds_read_b128 v[10:13], v169 offset:2048
	ds_read_b128 v[14:17], v169 offset:3072
	s_add_u32 s0, s30, 0x4000
	s_addc_u32 s1, s31, 0
	s_cmp_eq_u32 s53, 4
	s_cselect_b32 s38, s49, s0
	s_cselect_b32 s39, s23, s1
	s_cselect_b32 s34, s50, s51
	s_cselect_b32 s35, s21, s52
	s_add_u32 s36, s38, 0x8000
	s_addc_u32 s37, s39, 0
	v_lshl_add_u64 v[162:163], s[30:31], 0, v[156:157]
	s_add_i32 m0, s10, 0xc000
	ds_read_b128 v[174:177], v170
	ds_read_b128 v[178:181], v170 offset:1024
	ds_read_b128 v[182:185], v170 offset:2048
	ds_read_b128 v[186:189], v170 offset:3072
	ds_read_b128 v[190:193], v170 offset:4096
	ds_read_b128 v[194:197], v170 offset:5120
	ds_read_b128 v[198:201], v170 offset:6144
	ds_read_b128 v[202:205], v170 offset:7168
	global_load_lds_dwordx4 v[162:163], off
	v_lshl_add_u64 v[162:163], s[30:31], 0, v[154:155]
	s_add_i32 m0, s10, 0xe000
	s_nop 0
	global_load_lds_dwordx4 v[162:163], off
	s_waitcnt lgkmcnt(8)
	s_waitcnt vmcnt(10)
	s_barrier
	s_waitcnt lgkmcnt(0)
	s_waitcnt lgkmcnt(0)
	v_mfma_scale_f32_16x16x128_f8f6f4 v[142:145], v[2:9], v[174:181], v[142:145], v171, v171 op_sel_hi:[0,0,0]
	v_mfma_scale_f32_16x16x128_f8f6f4 v[138:141], v[10:17], v[174:181], v[138:141], v171, v171 op_sel_hi:[0,0,0]
	v_mfma_scale_f32_16x16x128_f8f6f4 v[126:129], v[2:9], v[182:189], v[126:129], v171, v171 op_sel_hi:[0,0,0]
	v_mfma_scale_f32_16x16x128_f8f6f4 v[122:125], v[10:17], v[182:189], v[122:125], v171, v171 op_sel_hi:[0,0,0]
	v_mfma_scale_f32_16x16x128_f8f6f4 v[110:113], v[2:9], v[190:197], v[110:113], v171, v171 op_sel_hi:[0,0,0]
	v_mfma_scale_f32_16x16x128_f8f6f4 v[106:109], v[10:17], v[190:197], v[106:109], v171, v171 op_sel_hi:[0,0,0]
	v_mfma_scale_f32_16x16x128_f8f6f4 v[94:97], v[2:9], v[198:205], v[94:97], v171, v171 op_sel_hi:[0,0,0]
	v_mfma_scale_f32_16x16x128_f8f6f4 v[90:93], v[10:17], v[198:205], v[90:93], v171, v171 op_sel_hi:[0,0,0]
	s_barrier
	s_add_i32 s0, s45, s9
	v_lshl_add_u64 v[162:163], s[34:35], 0, v[150:151]
	s_mov_b32 m0, s0
	ds_read_b128 v[206:209], v172
	ds_read_b128 v[210:213], v172 offset:1024
	ds_read_b128 v[214:217], v172 offset:2048
	ds_read_b128 v[218:221], v172 offset:3072
	global_load_lds_dwordx4 v[162:163], off
	v_lshl_add_u64 v[164:165], s[34:35], 0, v[146:147]
	s_add_i32 m0, s0, 0x2000
	s_nop 0
	global_load_lds_dwordx4 v[164:165], off
	s_waitcnt vmcnt(10)
	s_barrier
	s_waitcnt lgkmcnt(0)
	s_waitcnt lgkmcnt(0)
	v_mfma_scale_f32_16x16x128_f8f6f4 v[134:137], v[206:213], v[174:181], v[134:137], v171, v171 op_sel_hi:[0,0,0]
	v_mfma_scale_f32_16x16x128_f8f6f4 v[130:133], v[214:221], v[174:181], v[130:133], v171, v171 op_sel_hi:[0,0,0]
	v_mfma_scale_f32_16x16x128_f8f6f4 v[118:121], v[206:213], v[182:189], v[118:121], v171, v171 op_sel_hi:[0,0,0]
	v_mfma_scale_f32_16x16x128_f8f6f4 v[114:117], v[214:221], v[182:189], v[114:117], v171, v171 op_sel_hi:[0,0,0]
	v_mfma_scale_f32_16x16x128_f8f6f4 v[102:105], v[206:213], v[190:197], v[102:105], v171, v171 op_sel_hi:[0,0,0]
	v_mfma_scale_f32_16x16x128_f8f6f4 v[98:101], v[214:221], v[190:197], v[98:101], v171, v171 op_sel_hi:[0,0,0]
	v_mfma_scale_f32_16x16x128_f8f6f4 v[86:89], v[206:213], v[198:205], v[86:89], v171, v171 op_sel_hi:[0,0,0]
	v_mfma_scale_f32_16x16x128_f8f6f4 v[82:85], v[214:221], v[198:205], v[82:85], v171, v171 op_sel_hi:[0,0,0]
	s_mov_b32 m0, s10
	v_lshl_add_u64 v[222:223], s[38:39], 0, v[152:153]
	s_barrier
	ds_read_b128 v[174:177], v170 offset:16384
	ds_read_b128 v[178:181], v170 offset:17408
	ds_read_b128 v[182:185], v170 offset:18432
	ds_read_b128 v[186:189], v170 offset:19456
	ds_read_b128 v[190:193], v170 offset:20480
	ds_read_b128 v[194:197], v170 offset:21504
	ds_read_b128 v[198:201], v170 offset:22528
	ds_read_b128 v[202:205], v170 offset:23552
	global_load_lds_dwordx4 v[222:223], off
	v_lshl_add_u64 v[222:223], s[38:39], 0, v[148:149]
	s_mov_b32 m0, s11
	s_nop 0
	global_load_lds_dwordx4 v[222:223], off
	s_waitcnt vmcnt(10)
	s_barrier
	s_waitcnt lgkmcnt(0)
	s_waitcnt lgkmcnt(0)
	v_mfma_scale_f32_16x16x128_f8f6f4 v[78:81], v[2:9], v[174:181], v[78:81], v171, v171 op_sel_hi:[0,0,0]
	v_mfma_scale_f32_16x16x128_f8f6f4 v[74:77], v[10:17], v[174:181], v[74:77], v171, v171 op_sel_hi:[0,0,0]
	v_mfma_scale_f32_16x16x128_f8f6f4 v[62:65], v[2:9], v[182:189], v[62:65], v171, v171 op_sel_hi:[0,0,0]
	v_mfma_scale_f32_16x16x128_f8f6f4 v[58:61], v[10:17], v[182:189], v[58:61], v171, v171 op_sel_hi:[0,0,0]
	v_mfma_scale_f32_16x16x128_f8f6f4 v[46:49], v[2:9], v[190:197], v[46:49], v171, v171 op_sel_hi:[0,0,0]
	v_mfma_scale_f32_16x16x128_f8f6f4 v[42:45], v[10:17], v[190:197], v[42:45], v171, v171 op_sel_hi:[0,0,0]
	v_mfma_scale_f32_16x16x128_f8f6f4 v[30:33], v[2:9], v[198:205], v[30:33], v171, v171 op_sel_hi:[0,0,0]
	v_mfma_scale_f32_16x16x128_f8f6f4 v[26:29], v[10:17], v[198:205], v[26:29], v171, v171 op_sel_hi:[0,0,0]
	s_barrier
	s_add_u32 s0, s34, 0x20000
	s_addc_u32 s1, s35, 0
	s_add_i32 s54, s46, s9
	v_lshl_add_u64 v[2:3], s[0:1], 0, v[150:151]
	s_mov_b32 m0, s54
	s_nop 0
	global_load_lds_dwordx4 v[2:3], off
	v_lshl_add_u64 v[2:3], s[0:1], 0, v[146:147]
	s_add_i32 m0, s54, 0x2000
	s_nop 0
	global_load_lds_dwordx4 v[2:3], off
	s_waitcnt vmcnt(10)
	s_barrier
	v_mfma_scale_f32_16x16x128_f8f6f4 v[70:73], v[206:213], v[174:181], v[70:73], v171, v171 op_sel_hi:[0,0,0]
	v_mfma_scale_f32_16x16x128_f8f6f4 v[66:69], v[214:221], v[174:181], v[66:69], v171, v171 op_sel_hi:[0,0,0]
	v_mfma_scale_f32_16x16x128_f8f6f4 v[54:57], v[206:213], v[182:189], v[54:57], v171, v171 op_sel_hi:[0,0,0]
	v_mfma_scale_f32_16x16x128_f8f6f4 v[50:53], v[214:221], v[182:189], v[50:53], v171, v171 op_sel_hi:[0,0,0]
	v_mfma_scale_f32_16x16x128_f8f6f4 v[38:41], v[206:213], v[190:197], v[38:41], v171, v171 op_sel_hi:[0,0,0]
	v_mfma_scale_f32_16x16x128_f8f6f4 v[34:37], v[214:221], v[190:197], v[34:37], v171, v171 op_sel_hi:[0,0,0]
	v_mfma_scale_f32_16x16x128_f8f6f4 v[22:25], v[206:213], v[198:205], v[22:25], v171, v171 op_sel_hi:[0,0,0]
	v_mfma_scale_f32_16x16x128_f8f6f4 v[18:21], v[214:221], v[198:205], v[18:21], v171, v171 op_sel_hi:[0,0,0]
	s_add_i32 s54, 0, 0x18000
	v_add_u32_e32 v14, s54, v168
	s_barrier
	ds_read_b128 v[2:5], v14
	ds_read_b128 v[6:9], v14 offset:1024
	ds_read_b128 v[10:13], v14 offset:2048
	ds_read_b128 v[14:17], v14 offset:3072
	s_add_u32 s0, s38, 0x4000
	s_addc_u32 s1, s39, 0
	s_mov_b32 m0, s19
	v_lshl_add_u64 v[206:207], s[0:1], 0, v[152:153]
	ds_read_b128 v[174:177], v170 offset:32768
	ds_read_b128 v[178:181], v170 offset:33792
	ds_read_b128 v[182:185], v170 offset:34816
	ds_read_b128 v[186:189], v170 offset:35840
	ds_read_b128 v[190:193], v170 offset:36864
	ds_read_b128 v[194:197], v170 offset:37888
	ds_read_b128 v[198:201], v170 offset:38912
	ds_read_b128 v[202:205], v170 offset:39936
	global_load_lds_dwordx4 v[206:207], off
	v_lshl_add_u64 v[206:207], s[0:1], 0, v[148:149]
	s_mov_b32 m0, s29
	s_nop 0
	global_load_lds_dwordx4 v[206:207], off
	s_waitcnt lgkmcnt(8)
	s_waitcnt vmcnt(10)
	s_barrier
	s_waitcnt lgkmcnt(0)
	s_waitcnt lgkmcnt(0)
	v_mfma_scale_f32_16x16x128_f8f6f4 v[142:145], v[2:9], v[174:181], v[142:145], v171, v171 op_sel_hi:[0,0,0]
	v_mfma_scale_f32_16x16x128_f8f6f4 v[138:141], v[10:17], v[174:181], v[138:141], v171, v171 op_sel_hi:[0,0,0]
	v_mfma_scale_f32_16x16x128_f8f6f4 v[126:129], v[2:9], v[182:189], v[126:129], v171, v171 op_sel_hi:[0,0,0]
	v_mfma_scale_f32_16x16x128_f8f6f4 v[122:125], v[10:17], v[182:189], v[122:125], v171, v171 op_sel_hi:[0,0,0]
	v_mfma_scale_f32_16x16x128_f8f6f4 v[110:113], v[2:9], v[190:197], v[110:113], v171, v171 op_sel_hi:[0,0,0]
	v_mfma_scale_f32_16x16x128_f8f6f4 v[106:109], v[10:17], v[190:197], v[106:109], v171, v171 op_sel_hi:[0,0,0]
	v_mfma_scale_f32_16x16x128_f8f6f4 v[94:97], v[2:9], v[198:205], v[94:97], v171, v171 op_sel_hi:[0,0,0]
	v_mfma_scale_f32_16x16x128_f8f6f4 v[90:93], v[10:17], v[198:205], v[90:93], v171, v171 op_sel_hi:[0,0,0]
	s_barrier
	s_add_i32 s38, 0, 0x1c000
	s_add_i32 s0, s54, s9
	v_add_u32_e32 v218, s38, v168
	v_lshl_add_u64 v[162:163], v[162:163], 0, s[16:17]
	s_mov_b32 m0, s0
	ds_read_b128 v[206:209], v218
	ds_read_b128 v[210:213], v218 offset:1024
	ds_read_b128 v[214:217], v218 offset:2048
	ds_read_b128 v[218:221], v218 offset:3072
	global_load_lds_dwordx4 v[162:163], off
	v_lshl_add_u64 v[162:163], v[164:165], 0, s[16:17]
	s_add_i32 m0, s0, 0x2000
	s_nop 0
	global_load_lds_dwordx4 v[162:163], off
	s_waitcnt vmcnt(10)
	s_barrier
	s_waitcnt lgkmcnt(0)
	s_waitcnt lgkmcnt(0)
	v_mfma_scale_f32_16x16x128_f8f6f4 v[134:137], v[206:213], v[174:181], v[134:137], v171, v171 op_sel_hi:[0,0,0]
	v_mfma_scale_f32_16x16x128_f8f6f4 v[130:133], v[214:221], v[174:181], v[130:133], v171, v171 op_sel_hi:[0,0,0]
	v_mfma_scale_f32_16x16x128_f8f6f4 v[118:121], v[206:213], v[182:189], v[118:121], v171, v171 op_sel_hi:[0,0,0]
	v_mfma_scale_f32_16x16x128_f8f6f4 v[114:117], v[214:221], v[182:189], v[114:117], v171, v171 op_sel_hi:[0,0,0]
	v_mfma_scale_f32_16x16x128_f8f6f4 v[102:105], v[206:213], v[190:197], v[102:105], v171, v171 op_sel_hi:[0,0,0]
	v_mfma_scale_f32_16x16x128_f8f6f4 v[98:101], v[214:221], v[190:197], v[98:101], v171, v171 op_sel_hi:[0,0,0]
	v_mfma_scale_f32_16x16x128_f8f6f4 v[86:89], v[206:213], v[198:205], v[86:89], v171, v171 op_sel_hi:[0,0,0]
	v_mfma_scale_f32_16x16x128_f8f6f4 v[82:85], v[214:221], v[198:205], v[82:85], v171, v171 op_sel_hi:[0,0,0]
	s_mov_b32 m0, s43
	v_lshl_add_u64 v[162:163], s[36:37], 0, v[152:153]
	s_barrier
	ds_read_b128 v[174:177], v170 offset:49152
	ds_read_b128 v[178:181], v170 offset:50176
	ds_read_b128 v[182:185], v170 offset:51200
	ds_read_b128 v[186:189], v170 offset:52224
	ds_read_b128 v[190:193], v170 offset:53248
	ds_read_b128 v[194:197], v170 offset:54272
	ds_read_b128 v[198:201], v170 offset:55296
	ds_read_b128 v[202:205], v170 offset:56320
	global_load_lds_dwordx4 v[162:163], off
	v_lshl_add_u64 v[162:163], s[36:37], 0, v[148:149]
	s_mov_b32 m0, s44
	s_nop 0
	global_load_lds_dwordx4 v[162:163], off
	s_waitcnt vmcnt(10)
	s_barrier
	s_waitcnt lgkmcnt(0)
	s_waitcnt lgkmcnt(0)
	v_mfma_scale_f32_16x16x128_f8f6f4 v[78:81], v[2:9], v[174:181], v[78:81], v171, v171 op_sel_hi:[0,0,0]
	v_mfma_scale_f32_16x16x128_f8f6f4 v[74:77], v[10:17], v[174:181], v[74:77], v171, v171 op_sel_hi:[0,0,0]
	v_mfma_scale_f32_16x16x128_f8f6f4 v[62:65], v[2:9], v[182:189], v[62:65], v171, v171 op_sel_hi:[0,0,0]
	v_mfma_scale_f32_16x16x128_f8f6f4 v[58:61], v[10:17], v[182:189], v[58:61], v171, v171 op_sel_hi:[0,0,0]
	v_mfma_scale_f32_16x16x128_f8f6f4 v[46:49], v[2:9], v[190:197], v[46:49], v171, v171 op_sel_hi:[0,0,0]
	v_mfma_scale_f32_16x16x128_f8f6f4 v[42:45], v[10:17], v[190:197], v[42:45], v171, v171 op_sel_hi:[0,0,0]
	v_mfma_scale_f32_16x16x128_f8f6f4 v[30:33], v[2:9], v[198:205], v[30:33], v171, v171 op_sel_hi:[0,0,0]
	v_mfma_scale_f32_16x16x128_f8f6f4 v[26:29], v[10:17], v[198:205], v[26:29], v171, v171 op_sel_hi:[0,0,0]
	s_barrier
	s_add_u32 s0, s34, 0x20080
	s_addc_u32 s1, s35, 0
	s_add_i32 s34, s38, s9
	v_lshl_add_u64 v[2:3], s[0:1], 0, v[150:151]
	s_mov_b32 m0, s34
	s_nop 0
	global_load_lds_dwordx4 v[2:3], off
	v_lshl_add_u64 v[2:3], s[0:1], 0, v[146:147]
	s_add_i32 m0, s34, 0x2000
	s_nop 0
	global_load_lds_dwordx4 v[2:3], off
	s_waitcnt vmcnt(10)
	s_barrier
	v_mfma_scale_f32_16x16x128_f8f6f4 v[70:73], v[206:213], v[174:181], v[70:73], v171, v171 op_sel_hi:[0,0,0]
	v_mfma_scale_f32_16x16x128_f8f6f4 v[66:69], v[214:221], v[174:181], v[66:69], v171, v171 op_sel_hi:[0,0,0]
	v_mfma_scale_f32_16x16x128_f8f6f4 v[54:57], v[206:213], v[182:189], v[54:57], v171, v171 op_sel_hi:[0,0,0]
	v_mfma_scale_f32_16x16x128_f8f6f4 v[50:53], v[214:221], v[182:189], v[50:53], v171, v171 op_sel_hi:[0,0,0]
	v_mfma_scale_f32_16x16x128_f8f6f4 v[38:41], v[206:213], v[190:197], v[38:41], v171, v171 op_sel_hi:[0,0,0]
	v_mfma_scale_f32_16x16x128_f8f6f4 v[34:37], v[214:221], v[190:197], v[34:37], v171, v171 op_sel_hi:[0,0,0]
	v_mfma_scale_f32_16x16x128_f8f6f4 v[22:25], v[206:213], v[198:205], v[22:25], v171, v171 op_sel_hi:[0,0,0]
	v_mfma_scale_f32_16x16x128_f8f6f4 v[18:21], v[214:221], v[198:205], v[18:21], v171, v171 op_sel_hi:[0,0,0]
	s_add_i32 s53, s53, 2
	s_add_u32 s51, s51, 0x100
	s_addc_u32 s52, s52, 0
	s_add_u32 s30, s30, 0x10000
	s_addc_u32 s31, s31, 0
	s_cmp_gt_u32 s53, 5
	s_barrier
	s_cbranch_scc0 .LBB0_2108
	v_pk_mul_f32 v[10:11], v[142:143], s[18:19] op_sel_hi:[1,0]
	v_pk_mul_f32 v[8:9], v[144:145], s[18:19] op_sel_hi:[1,0]
	v_med3_f32 v5, v10, s47, v173
	v_med3_f32 v11, v11, s47, v173
	v_mov_b32_e32 v10, 0
	v_cvt_pk_fp8_f32 v10, v5, v11
	v_mov_b32_e32 v3, v166
	v_mov_b32_e32 v2, v167
	s_lshl_b32 s0, s48, 8
	v_pk_mul_f32 v[14:15], v[138:139], s[18:19] op_sel_hi:[1,0]
	v_med3_f32 v5, v8, s47, v173
	v_med3_f32 v8, v9, s47, v173
	s_nop 15
	s_nop 15
	s_or_b32 s0, s0, s42
	v_cvt_pk_fp8_f32 v10, v5, v8 op_sel:[0,0,1]
	v_med3_f32 v5, v14, s47, v173
	v_med3_f32 v8, v15, s47, v173
	v_mov_b32_e32 v11, 0
	v_lshl_add_u32 v2, v2, 3, s0
	s_lshl_b32 s0, s28, 8
	v_cvt_pk_fp8_f32 v11, v5, v8
	s_add_i32 s0, s0, s41
	v_add_u32_e32 v4, s0, v3
	v_pk_mul_f32 v[12:13], v[140:141], s[18:19] op_sel_hi:[1,0]
	v_mov_b32_e32 v6, v4
	v_med3_f32 v5, v12, s47, v173
	v_med3_f32 v8, v13, s47, v173
	v_cvt_pk_fp8_f32 v11, v5, v8 op_sel:[0,0,1]
	v_ashrrev_i32_e32 v7, 31, v6
	v_lshlrev_b64 v[6:7], 10, v[6:7]
	v_ashrrev_i32_e32 v3, 31, v2
	v_lshl_add_u64 v[6:7], s[14:15], 0, v[6:7]
	v_lshl_add_u64 v[6:7], v[6:7], 0, v[2:3]
	global_store_dwordx2 v[6:7], v[10:11], off
	v_pk_mul_f32 v[10:11], v[134:135], s[18:19] op_sel_hi:[1,0]
	v_pk_mul_f32 v[8:9], v[136:137], s[18:19] op_sel_hi:[1,0]
	v_med3_f32 v5, v10, s47, v173
	v_med3_f32 v11, v11, s47, v173
	v_mov_b32_e32 v10, 0
	v_cvt_pk_fp8_f32 v10, v5, v11
	v_pk_mul_f32 v[14:15], v[130:131], s[18:19] op_sel_hi:[1,0]
	v_med3_f32 v5, v8, s47, v173
	v_med3_f32 v8, v9, s47, v173
	v_cvt_pk_fp8_f32 v10, v5, v8 op_sel:[0,0,1]
	v_med3_f32 v5, v14, s47, v173
	v_med3_f32 v8, v15, s47, v173
	v_mov_b32_e32 v11, 0
	v_cvt_pk_fp8_f32 v11, v5, v8
	v_pk_mul_f32 v[12:13], v[132:133], s[18:19] op_sel_hi:[1,0]
	v_pk_mul_f32 v[14:15], v[122:123], s[18:19] op_sel_hi:[1,0]
	v_med3_f32 v5, v12, s47, v173
	v_med3_f32 v8, v13, s47, v173
	v_cvt_pk_fp8_f32 v11, v5, v8 op_sel:[0,0,1]
	v_pk_mul_f32 v[8:9], v[128:129], s[18:19] op_sel_hi:[1,0]
	v_pk_mul_f32 v[12:13], v[124:125], s[18:19] op_sel_hi:[1,0]
	s_and_b64 vcc, exec, s[12:13]
	global_store_dwordx2 v[6:7], v[10:11], off offset:128
	v_pk_mul_f32 v[10:11], v[126:127], s[18:19] op_sel_hi:[1,0]
	v_add_u32_e32 v6, 16, v4
	v_med3_f32 v5, v10, s47, v173
	v_med3_f32 v11, v11, s47, v173
	v_mov_b32_e32 v10, 0
	v_cvt_pk_fp8_f32 v10, v5, v11
	v_med3_f32 v5, v8, s47, v173
	v_med3_f32 v8, v9, s47, v173
	v_mov_b32_e32 v11, 0
	v_cvt_pk_fp8_f32 v10, v5, v8 op_sel:[0,0,1]
	v_med3_f32 v5, v14, s47, v173
	v_med3_f32 v8, v15, s47, v173
	v_cvt_pk_fp8_f32 v11, v5, v8
	v_med3_f32 v5, v12, s47, v173
	v_med3_f32 v8, v13, s47, v173
	v_cvt_pk_fp8_f32 v11, v5, v8 op_sel:[0,0,1]
	v_ashrrev_i32_e32 v7, 31, v6
	v_lshlrev_b64 v[6:7], 10, v[6:7]
	v_lshl_add_u64 v[6:7], s[14:15], 0, v[6:7]
	v_lshl_add_u64 v[6:7], v[6:7], 0, v[2:3]
	global_store_dwordx2 v[6:7], v[10:11], off
	v_pk_mul_f32 v[10:11], v[118:119], s[18:19] op_sel_hi:[1,0]
	v_pk_mul_f32 v[8:9], v[120:121], s[18:19] op_sel_hi:[1,0]
	v_med3_f32 v5, v10, s47, v173
	v_med3_f32 v11, v11, s47, v173
	v_mov_b32_e32 v10, 0
	v_cvt_pk_fp8_f32 v10, v5, v11
	v_pk_mul_f32 v[14:15], v[114:115], s[18:19] op_sel_hi:[1,0]
	v_med3_f32 v5, v8, s47, v173
	v_med3_f32 v8, v9, s47, v173
	v_cvt_pk_fp8_f32 v10, v5, v8 op_sel:[0,0,1]
	v_med3_f32 v5, v14, s47, v173
	v_med3_f32 v8, v15, s47, v173
	v_mov_b32_e32 v11, 0
	v_cvt_pk_fp8_f32 v11, v5, v8
	v_pk_mul_f32 v[12:13], v[116:117], s[18:19] op_sel_hi:[1,0]
	v_pk_mul_f32 v[14:15], v[106:107], s[18:19] op_sel_hi:[1,0]
	v_med3_f32 v5, v12, s47, v173
	v_med3_f32 v8, v13, s47, v173
	v_cvt_pk_fp8_f32 v11, v5, v8 op_sel:[0,0,1]
	v_pk_mul_f32 v[8:9], v[112:113], s[18:19] op_sel_hi:[1,0]
	v_pk_mul_f32 v[12:13], v[108:109], s[18:19] op_sel_hi:[1,0]
	s_mov_b32 s48, s20
	global_store_dwordx2 v[6:7], v[10:11], off offset:128
	v_pk_mul_f32 v[10:11], v[110:111], s[18:19] op_sel_hi:[1,0]
	v_add_u32_e32 v6, 32, v4
	v_med3_f32 v5, v10, s47, v173
	v_med3_f32 v11, v11, s47, v173
	v_mov_b32_e32 v10, 0
	v_cvt_pk_fp8_f32 v10, v5, v11
	v_med3_f32 v5, v8, s47, v173
	v_med3_f32 v8, v9, s47, v173
	v_mov_b32_e32 v11, 0
	v_cvt_pk_fp8_f32 v10, v5, v8 op_sel:[0,0,1]
	v_med3_f32 v5, v14, s47, v173
	v_med3_f32 v8, v15, s47, v173
	v_cvt_pk_fp8_f32 v11, v5, v8
	v_med3_f32 v5, v12, s47, v173
	v_med3_f32 v8, v13, s47, v173
	v_cvt_pk_fp8_f32 v11, v5, v8 op_sel:[0,0,1]
	v_ashrrev_i32_e32 v7, 31, v6
	v_lshlrev_b64 v[6:7], 10, v[6:7]
	v_lshl_add_u64 v[6:7], s[14:15], 0, v[6:7]
	v_lshl_add_u64 v[6:7], v[6:7], 0, v[2:3]
	global_store_dwordx2 v[6:7], v[10:11], off
	v_pk_mul_f32 v[10:11], v[102:103], s[18:19] op_sel_hi:[1,0]
	v_pk_mul_f32 v[8:9], v[104:105], s[18:19] op_sel_hi:[1,0]
	v_med3_f32 v5, v10, s47, v173
	v_med3_f32 v11, v11, s47, v173
	v_mov_b32_e32 v10, 0
	v_cvt_pk_fp8_f32 v10, v5, v11
	v_pk_mul_f32 v[14:15], v[98:99], s[18:19] op_sel_hi:[1,0]
	v_med3_f32 v5, v8, s47, v173
	v_med3_f32 v8, v9, s47, v173
	v_cvt_pk_fp8_f32 v10, v5, v8 op_sel:[0,0,1]
	v_med3_f32 v5, v14, s47, v173
	v_med3_f32 v8, v15, s47, v173
	v_mov_b32_e32 v11, 0
	v_cvt_pk_fp8_f32 v11, v5, v8
	v_pk_mul_f32 v[12:13], v[100:101], s[18:19] op_sel_hi:[1,0]
	v_pk_mul_f32 v[14:15], v[90:91], s[18:19] op_sel_hi:[1,0]
	v_med3_f32 v5, v12, s47, v173
	v_med3_f32 v8, v13, s47, v173
	v_cvt_pk_fp8_f32 v11, v5, v8 op_sel:[0,0,1]
	v_pk_mul_f32 v[8:9], v[96:97], s[18:19] op_sel_hi:[1,0]
	v_pk_mul_f32 v[12:13], v[92:93], s[18:19] op_sel_hi:[1,0]
	s_mov_b32 s28, s22
	global_store_dwordx2 v[6:7], v[10:11], off offset:128
	v_pk_mul_f32 v[10:11], v[94:95], s[18:19] op_sel_hi:[1,0]
	v_add_u32_e32 v6, 48, v4
	v_med3_f32 v5, v10, s47, v173
	v_med3_f32 v11, v11, s47, v173
	v_mov_b32_e32 v10, 0
	v_cvt_pk_fp8_f32 v10, v5, v11
	v_med3_f32 v5, v8, s47, v173
	v_med3_f32 v8, v9, s47, v173
	v_mov_b32_e32 v11, 0
	v_cvt_pk_fp8_f32 v10, v5, v8 op_sel:[0,0,1]
	v_med3_f32 v5, v14, s47, v173
	v_med3_f32 v8, v15, s47, v173
	v_cvt_pk_fp8_f32 v11, v5, v8
	v_med3_f32 v5, v12, s47, v173
	v_med3_f32 v8, v13, s47, v173
	v_cvt_pk_fp8_f32 v11, v5, v8 op_sel:[0,0,1]
	v_ashrrev_i32_e32 v7, 31, v6
	v_lshlrev_b64 v[6:7], 10, v[6:7]
	v_lshl_add_u64 v[6:7], s[14:15], 0, v[6:7]
	v_lshl_add_u64 v[6:7], v[6:7], 0, v[2:3]
	global_store_dwordx2 v[6:7], v[10:11], off
	v_pk_mul_f32 v[10:11], v[86:87], s[18:19] op_sel_hi:[1,0]
	v_pk_mul_f32 v[8:9], v[88:89], s[18:19] op_sel_hi:[1,0]
	v_med3_f32 v5, v10, s47, v173
	v_med3_f32 v11, v11, s47, v173
	v_mov_b32_e32 v10, 0
	v_cvt_pk_fp8_f32 v10, v5, v11
	v_pk_mul_f32 v[14:15], v[82:83], s[18:19] op_sel_hi:[1,0]
	v_med3_f32 v5, v8, s47, v173
	v_med3_f32 v8, v9, s47, v173
	v_cvt_pk_fp8_f32 v10, v5, v8 op_sel:[0,0,1]
	v_med3_f32 v5, v14, s47, v173
	v_med3_f32 v8, v15, s47, v173
	v_mov_b32_e32 v11, 0
	v_cvt_pk_fp8_f32 v11, v5, v8
	v_pk_mul_f32 v[12:13], v[84:85], s[18:19] op_sel_hi:[1,0]
	v_pk_mul_f32 v[14:15], v[74:75], s[18:19] op_sel_hi:[1,0]
	v_med3_f32 v5, v12, s47, v173
	v_med3_f32 v8, v13, s47, v173
	v_cvt_pk_fp8_f32 v11, v5, v8 op_sel:[0,0,1]
	v_pk_mul_f32 v[8:9], v[80:81], s[18:19] op_sel_hi:[1,0]
	v_pk_mul_f32 v[12:13], v[76:77], s[18:19] op_sel_hi:[1,0]
	s_mov_b64 s[30:31], s[26:27]
	global_store_dwordx2 v[6:7], v[10:11], off offset:128
	v_pk_mul_f32 v[10:11], v[78:79], s[18:19] op_sel_hi:[1,0]
	v_add_u32_e32 v6, 0x80, v4
	v_med3_f32 v5, v10, s47, v173
	v_med3_f32 v11, v11, s47, v173
	v_mov_b32_e32 v10, 0
	v_cvt_pk_fp8_f32 v10, v5, v11
	v_med3_f32 v5, v8, s47, v173
	v_med3_f32 v8, v9, s47, v173
	v_mov_b32_e32 v11, 0
	v_cvt_pk_fp8_f32 v10, v5, v8 op_sel:[0,0,1]
	v_med3_f32 v5, v14, s47, v173
	v_med3_f32 v8, v15, s47, v173
	v_cvt_pk_fp8_f32 v11, v5, v8
	v_med3_f32 v5, v12, s47, v173
	v_med3_f32 v8, v13, s47, v173
	v_cvt_pk_fp8_f32 v11, v5, v8 op_sel:[0,0,1]
	v_ashrrev_i32_e32 v7, 31, v6
	v_lshlrev_b64 v[6:7], 10, v[6:7]
	v_lshl_add_u64 v[6:7], s[14:15], 0, v[6:7]
	v_lshl_add_u64 v[6:7], v[6:7], 0, v[2:3]
	global_store_dwordx2 v[6:7], v[10:11], off
	v_pk_mul_f32 v[10:11], v[70:71], s[18:19] op_sel_hi:[1,0]
	v_pk_mul_f32 v[8:9], v[72:73], s[18:19] op_sel_hi:[1,0]
	v_med3_f32 v5, v10, s47, v173
	v_med3_f32 v11, v11, s47, v173
	v_mov_b32_e32 v10, 0
	v_cvt_pk_fp8_f32 v10, v5, v11
	v_pk_mul_f32 v[14:15], v[66:67], s[18:19] op_sel_hi:[1,0]
	v_med3_f32 v5, v8, s47, v173
	v_med3_f32 v8, v9, s47, v173
	v_cvt_pk_fp8_f32 v10, v5, v8 op_sel:[0,0,1]
	v_med3_f32 v5, v14, s47, v173
	v_med3_f32 v8, v15, s47, v173
	v_mov_b32_e32 v11, 0
	v_cvt_pk_fp8_f32 v11, v5, v8
	v_pk_mul_f32 v[12:13], v[68:69], s[18:19] op_sel_hi:[1,0]
	v_pk_mul_f32 v[14:15], v[58:59], s[18:19] op_sel_hi:[1,0]
	v_med3_f32 v5, v12, s47, v173
	v_med3_f32 v8, v13, s47, v173
	v_cvt_pk_fp8_f32 v11, v5, v8 op_sel:[0,0,1]
	v_pk_mul_f32 v[8:9], v[64:65], s[18:19] op_sel_hi:[1,0]
	v_pk_mul_f32 v[12:13], v[60:61], s[18:19] op_sel_hi:[1,0]
	s_mov_b64 s[34:35], s[24:25]
	global_store_dwordx2 v[6:7], v[10:11], off offset:128
	v_pk_mul_f32 v[10:11], v[62:63], s[18:19] op_sel_hi:[1,0]
	v_add_u32_e32 v6, 0x90, v4
	v_med3_f32 v5, v10, s47, v173
	v_med3_f32 v11, v11, s47, v173
	v_mov_b32_e32 v10, 0
	v_cvt_pk_fp8_f32 v10, v5, v11
	v_med3_f32 v5, v8, s47, v173
	v_med3_f32 v8, v9, s47, v173
	v_mov_b32_e32 v11, 0
	v_cvt_pk_fp8_f32 v10, v5, v8 op_sel:[0,0,1]
	v_med3_f32 v5, v14, s47, v173
	v_med3_f32 v8, v15, s47, v173
	v_cvt_pk_fp8_f32 v11, v5, v8
	v_med3_f32 v5, v12, s47, v173
	v_med3_f32 v8, v13, s47, v173
	v_cvt_pk_fp8_f32 v11, v5, v8 op_sel:[0,0,1]
	v_ashrrev_i32_e32 v7, 31, v6
	v_lshlrev_b64 v[6:7], 10, v[6:7]
	v_lshl_add_u64 v[6:7], s[14:15], 0, v[6:7]
	v_lshl_add_u64 v[6:7], v[6:7], 0, v[2:3]
	global_store_dwordx2 v[6:7], v[10:11], off
	v_pk_mul_f32 v[10:11], v[54:55], s[18:19] op_sel_hi:[1,0]
	v_pk_mul_f32 v[8:9], v[56:57], s[18:19] op_sel_hi:[1,0]
	v_med3_f32 v5, v10, s47, v173
	v_med3_f32 v11, v11, s47, v173
	v_mov_b32_e32 v10, 0
	v_cvt_pk_fp8_f32 v10, v5, v11
	v_pk_mul_f32 v[14:15], v[50:51], s[18:19] op_sel_hi:[1,0]
	v_med3_f32 v5, v8, s47, v173
	v_med3_f32 v8, v9, s47, v173
	v_cvt_pk_fp8_f32 v10, v5, v8 op_sel:[0,0,1]
	v_med3_f32 v5, v14, s47, v173
	v_med3_f32 v8, v15, s47, v173
	v_mov_b32_e32 v11, 0
	v_cvt_pk_fp8_f32 v11, v5, v8
	v_pk_mul_f32 v[12:13], v[52:53], s[18:19] op_sel_hi:[1,0]
	v_pk_mul_f32 v[14:15], v[42:43], s[18:19] op_sel_hi:[1,0]
	v_med3_f32 v5, v12, s47, v173
	v_med3_f32 v8, v13, s47, v173
	v_cvt_pk_fp8_f32 v11, v5, v8 op_sel:[0,0,1]
	v_pk_mul_f32 v[8:9], v[48:49], s[18:19] op_sel_hi:[1,0]
	v_pk_mul_f32 v[12:13], v[44:45], s[18:19] op_sel_hi:[1,0]
	global_store_dwordx2 v[6:7], v[10:11], off offset:128
	v_pk_mul_f32 v[10:11], v[46:47], s[18:19] op_sel_hi:[1,0]
	v_add_u32_e32 v6, 0xa0, v4
	v_med3_f32 v5, v10, s47, v173
	v_med3_f32 v11, v11, s47, v173
	v_mov_b32_e32 v10, 0
	v_cvt_pk_fp8_f32 v10, v5, v11
	v_med3_f32 v5, v8, s47, v173
	v_med3_f32 v8, v9, s47, v173
	v_mov_b32_e32 v11, 0
	v_cvt_pk_fp8_f32 v10, v5, v8 op_sel:[0,0,1]
	v_med3_f32 v5, v14, s47, v173
	v_med3_f32 v8, v15, s47, v173
	v_cvt_pk_fp8_f32 v11, v5, v8
	v_med3_f32 v5, v12, s47, v173
	v_med3_f32 v8, v13, s47, v173
	v_cvt_pk_fp8_f32 v11, v5, v8 op_sel:[0,0,1]
	v_ashrrev_i32_e32 v7, 31, v6
	v_lshlrev_b64 v[6:7], 10, v[6:7]
	v_lshl_add_u64 v[6:7], s[14:15], 0, v[6:7]
	v_lshl_add_u64 v[6:7], v[6:7], 0, v[2:3]
	global_store_dwordx2 v[6:7], v[10:11], off
	v_pk_mul_f32 v[10:11], v[38:39], s[18:19] op_sel_hi:[1,0]
	v_pk_mul_f32 v[8:9], v[40:41], s[18:19] op_sel_hi:[1,0]
	v_med3_f32 v5, v10, s47, v173
	v_med3_f32 v11, v11, s47, v173
	v_mov_b32_e32 v10, 0
	v_cvt_pk_fp8_f32 v10, v5, v11
	v_pk_mul_f32 v[14:15], v[34:35], s[18:19] op_sel_hi:[1,0]
	v_med3_f32 v5, v8, s47, v173
	v_med3_f32 v8, v9, s47, v173
	v_cvt_pk_fp8_f32 v10, v5, v8 op_sel:[0,0,1]
	v_med3_f32 v5, v14, s47, v173
	v_med3_f32 v8, v15, s47, v173
	v_mov_b32_e32 v11, 0
	v_cvt_pk_fp8_f32 v11, v5, v8
	v_pk_mul_f32 v[12:13], v[36:37], s[18:19] op_sel_hi:[1,0]
	v_add_u32_e32 v4, 0xb0, v4
	v_med3_f32 v5, v12, s47, v173
	v_med3_f32 v8, v13, s47, v173
	v_cvt_pk_fp8_f32 v11, v5, v8 op_sel:[0,0,1]
	v_pk_mul_f32 v[8:9], v[28:29], s[18:19] op_sel_hi:[1,0]
	global_store_dwordx2 v[6:7], v[10:11], off offset:128
	v_pk_mul_f32 v[6:7], v[30:31], s[18:19] op_sel_hi:[1,0]
	v_pk_mul_f32 v[10:11], v[26:27], s[18:19] op_sel_hi:[1,0]
	v_ashrrev_i32_e32 v5, 31, v4
	v_med3_f32 v12, v6, s47, v173
	v_med3_f32 v7, v7, s47, v173
	v_mov_b32_e32 v6, 0
	v_lshlrev_b64 v[4:5], 10, v[4:5]
	v_cvt_pk_fp8_f32 v6, v12, v7
	v_lshl_add_u64 v[4:5], s[14:15], 0, v[4:5]
	v_lshl_add_u64 v[2:3], v[4:5], 0, v[2:3]
	v_pk_mul_f32 v[4:5], v[32:33], s[18:19] op_sel_hi:[1,0]
	v_mov_b32_e32 v7, 0
	v_med3_f32 v4, v4, s47, v173
	v_med3_f32 v5, v5, s47, v173
	v_cvt_pk_fp8_f32 v6, v4, v5 op_sel:[0,0,1]
	v_med3_f32 v4, v10, s47, v173
	v_med3_f32 v5, v11, s47, v173
	v_cvt_pk_fp8_f32 v7, v4, v5
	v_med3_f32 v4, v8, s47, v173
	v_med3_f32 v5, v9, s47, v173
	v_pk_mul_f32 v[10:11], v[18:19], s[18:19] op_sel_hi:[1,0]
	v_cvt_pk_fp8_f32 v7, v4, v5 op_sel:[0,0,1]
	v_pk_mul_f32 v[4:5], v[24:25], s[18:19] op_sel_hi:[1,0]
	v_pk_mul_f32 v[8:9], v[20:21], s[18:19] op_sel_hi:[1,0]
	v_med3_f32 v4, v4, s47, v173
	global_store_dwordx2 v[2:3], v[6:7], off
	v_pk_mul_f32 v[6:7], v[22:23], s[18:19] op_sel_hi:[1,0]
	v_med3_f32 v5, v5, s47, v173
	v_med3_f32 v12, v6, s47, v173
	v_med3_f32 v7, v7, s47, v173
	v_mov_b32_e32 v6, 0
	v_cvt_pk_fp8_f32 v6, v12, v7
	v_mov_b32_e32 v7, 0
	v_cvt_pk_fp8_f32 v6, v4, v5 op_sel:[0,0,1]
	v_med3_f32 v4, v10, s47, v173
	v_med3_f32 v5, v11, s47, v173
	v_cvt_pk_fp8_f32 v7, v4, v5
	v_med3_f32 v4, v8, s47, v173
	v_med3_f32 v5, v9, s47, v173
	v_cvt_pk_fp8_f32 v7, v4, v5 op_sel:[0,0,1]
	global_store_dwordx2 v[2:3], v[6:7], off offset:128
	s_cbranch_vccz .LBB0_2101
	s_waitcnt vmcnt(0)
	s_cmpk_gt_u32 s4, 0xff
	s_cbranch_scc1 .LBB0_2112
	s_barrier

.LBB0_2166:
	s_or_b64 exec, exec, s[12:13]
	s_waitcnt lgkmcnt(0)
	s_barrier
	s_load_dwordx8 s[16:23], s[84:85], 0xd8
	s_load_dwordx4 s[8:11], s[84:85], 0xf8
	s_load_dwordx2 s[0:1], s[84:85], 0x108
	v_mov_b32_e32 v45, v0
	v_mov_b32_e32 v35, 0
	v_and_b32_e32 v74, 63, v45
	s_waitcnt lgkmcnt(0)
	s_mov_b32 s6, s0
	s_mov_b32 s0, s10
	s_add_u32 s24, s6, 0x3e00000
	s_addc_u32 s25, s1, 0
	v_lshlrev_b32_e32 v34, 4, v74
	v_lshl_add_u64 v[2:3], s[22:23], 0, v[34:35]
	s_mov_b64 s[4:5], 0x5000
	s_movk_i32 s0, 0x5000
	s_add_u32 s22, s6, 0x3900000
	v_lshl_add_u64 v[26:27], v[2:3], 0, s[4:5]
	v_add_co_u32_e32 v2, vcc, s0, v2
	s_addc_u32 s23, s1, 0
	v_lshl_add_u64 v[6:7], s[8:9], 0, v[34:35]
	v_addc_co_u32_e32 v3, vcc, 0, v3, vcc
	s_add_u32 s14, s6, 0xa100000
	s_mov_b32 s7, s1
	v_lshl_add_u64 v[30:31], v[6:7], 0, s[4:5]
	v_add_co_u32_e32 v6, vcc, s0, v6
	s_addc_u32 s15, s1, 0
	v_readlane_b32 s0, v253, 36
	v_readlane_b32 s1, v253, 37
	s_add_u32 s0, s14, s0
	s_addc_u32 s1, s15, s1
	v_readlane_b32 s4, v253, 38
	v_readlane_b32 s5, v253, 39
	s_add_u32 s4, s14, s4
	s_addc_u32 s5, s15, s5
	v_lshlrev_b32_e32 v34, 3, v74
	v_addc_co_u32_e32 v7, vcc, 0, v7, vcc
	v_lshl_add_u64 v[42:43], s[0:1], 0, v[34:35]
	v_lshl_add_u64 v[46:47], s[4:5], 0, v[34:35]
	global_load_dwordx4 v[2:5], v[2:3], off nt
	s_nop 0
	global_load_dwordx4 v[6:9], v[6:7], off nt
	s_nop 0
	global_load_dwordx4 v[10:13], v[26:27], off offset:1024
	global_load_dwordx4 v[14:17], v[30:31], off offset:1024
	global_load_dwordx4 v[18:21], v[26:27], off offset:2048
	global_load_dwordx4 v[22:25], v[30:31], off offset:2048
	s_nop 0
	global_load_dwordx4 v[26:29], v[26:27], off offset:3072
	s_nop 0
	global_load_dwordx4 v[30:33], v[30:31], off offset:3072
	v_cmp_gt_u32_e64 s[12:13], 16, v74
	global_load_dwordx2 v[62:63], v[42:43], off
	global_load_dwordx2 v[36:37], v[46:47], off
	global_load_dwordx2 v[64:65], v[42:43], off offset:512
	global_load_dwordx2 v[38:39], v[46:47], off offset:512
	global_load_dwordx2 v[60:61], v[42:43], off offset:1024
	global_load_dwordx2 v[40:41], v[46:47], off offset:1024
	global_load_dwordx2 v[58:59], v[42:43], off offset:1536
	s_nop 0
	global_load_dwordx2 v[42:43], v[46:47], off offset:1536
	v_mov_b32_e32 v75, -1
	v_lshlrev_b32_e32 v44, 11, v74
	v_mov_b32_e32 v82, v35
	v_mov_b32_e32 v81, -1
	s_and_saveexec_b64 s[26:27], s[12:13]
	s_cbranch_execz .LBB0_2168
	v_readlane_b32 s0, v253, 34
	v_readlane_b32 s1, v253, 35
	s_mov_b32 s4, s0
	s_ashr_i32 s0, s0, 11
	s_ashr_i32 s1, s0, 31
	s_lshl_b64 s[0:1], s[0:1], 15
	s_and_b32 s4, s4, 0x7ff
	s_or_b32 s0, s0, s4
	s_ashr_i32 s4, s68, 11
	s_ashr_i32 s5, s4, 31
	s_lshl_b64 s[4:5], s[4:5], 15
	s_and_b32 s8, s68, 0x7ff
	s_or_b32 s4, s4, s8
	v_or_b32_e32 v46, s4, v44
	v_mov_b32_e32 v47, s5
	v_lshl_add_u64 v[48:49], v[46:47], 1, s[24:25]
	v_lshl_add_u64 v[46:47], v[46:47], 2, s[22:23]
	global_load_sshort v81, v[48:49], off
	global_load_dword v82, v[46:47], off
	v_or_b32_e32 v46, s0, v44
	v_mov_b32_e32 v47, s1
	v_lshl_add_u64 v[48:49], v[46:47], 1, s[24:25]
	v_lshl_add_u64 v[46:47], v[46:47], 2, s[22:23]
	global_load_sshort v75, v[48:49], off
	global_load_dword v35, v[46:47], off

.LBB0_2170:
	v_mov_b32_e32 v82, v71
	v_mov_b32_e32 v83, v68
	v_mov_b32_e32 v84, v70
	v_mov_b32_e32 v85, v69
	v_pk_add_f32 v[82:83], v[82:83], v[84:85]
	v_mov_b32_e32 v84, v67
	v_mov_b32_e32 v85, v62
	v_mov_b32_e32 v86, v66
	v_mov_b32_e32 v87, v63
	v_pk_add_f32 v[84:85], v[84:85], v[86:87]
	v_add_f32_e32 v34, v82, v83
	v_pk_add_f32 v[84:85], v[84:85], v[84:85] op_sel_hi:[0,1]
	v_add_f32_e32 v83, 0, v34
	v_add_f32_e32 v87, v64, v65
	v_add_f32_e32 v89, v60, v61
	v_mov_b32_e32 v86, v58
	v_mov_b32_e32 v88, v59
	v_mov_b32_e32 v84, v72
	v_mov_b32_e32 v82, v73
	v_pk_add_f32 v[86:87], v[86:87], v[88:89]
	v_pk_add_f32 v[82:83], v[84:85], v[82:83]
	s_ashr_i32 s31, s30, 31
	v_pk_add_f32 v[82:83], v[86:87], v[82:83]
	s_nop 0
	v_add_f32_e32 v34, v82, v83
	s_nop 1
	v_add_f32_dpp v34, v34, v34 quad_perm:[1,0,3,2] row_mask:0xf bank_mask:0xf bound_ctrl:1
	s_nop 1
	v_add_f32_dpp v34, v34, v34 quad_perm:[2,3,0,1] row_mask:0xf bank_mask:0xf bound_ctrl:1
	s_nop 1
	v_add_f32_dpp v34, v34, v34 row_half_mirror row_mask:0xf bank_mask:0xf bound_ctrl:1
	s_nop 1
	v_add_f32_dpp v34, v34, v34 row_mirror row_mask:0xf bank_mask:0xf bound_ctrl:1
	s_nop 0
	v_readlane_b32 s8, v34, 16
	v_readlane_b32 s9, v34, 48
	v_readlane_b32 s0, v34, 0
	v_readlane_b32 s1, v34, 32
	v_mov_b32_e32 v82, s8
	v_mov_b32_e32 v83, s9
	v_pk_add_f32 v[82:83], s[0:1], v[82:83]
	s_nop 0
	v_add_f32_e32 v46, v82, v83
	v_fmac_f32_e32 v71, 0xba800000, v46
	v_fmac_f32_e32 v70, 0xba800000, v46
	v_fmac_f32_e32 v69, 0xba800000, v46
	v_fmac_f32_e32 v68, 0xba800000, v46
	v_pk_mul_f32 v[82:83], v[68:69], v[68:69]
	v_pk_mul_f32 v[84:85], v[70:71], v[70:71]
	v_fmac_f32_e32 v67, 0xba800000, v46
	v_pk_mov_b32 v[86:87], v[84:85], v[82:83] op_sel:[1,0]
	v_mov_b32_e32 v85, v83
	v_fmac_f32_e32 v66, 0xba800000, v46
	v_fmac_f32_e32 v63, 0xba800000, v46
	v_fmac_f32_e32 v62, 0xba800000, v46
	v_pk_add_f32 v[82:83], v[86:87], v[84:85]
	v_pk_mul_f32 v[84:85], v[62:63], v[62:63]
	v_pk_mul_f32 v[86:87], v[66:67], v[66:67]
	v_fmac_f32_e32 v64, 0xba800000, v46
	v_pk_mov_b32 v[88:89], v[86:87], v[84:85] op_sel:[1,0]
	v_mov_b32_e32 v87, v85
	v_fmac_f32_e32 v65, 0xba800000, v46
	v_fmac_f32_e32 v60, 0xba800000, v46
	v_mul_f32_e32 v34, v64, v64
	v_pk_add_f32 v[84:85], v[88:89], v[86:87]
	v_fmac_f32_e32 v61, 0xba800000, v46
	v_pk_fma_f32 v[86:87], v[64:65], v[64:65], v[34:35] op_sel_hi:[1,1,0]
	v_mul_f32_e32 v34, v60, v60
	v_pk_add_f32 v[82:83], v[82:83], v[82:83] op_sel_hi:[0,1]
	v_pk_add_f32 v[84:85], v[84:85], v[84:85] op_sel_hi:[0,1]
	v_pk_fma_f32 v[88:89], v[60:61], v[60:61], v[34:35] op_sel_hi:[1,1,0]
	v_fmamk_f32 v73, v46, 0xba800000, v73
	v_fmamk_f32 v72, v46, 0xba800000, v72
	v_fmamk_f32 v59, v46, 0xba800000, v59
	v_fmac_f32_e32 v58, 0xba800000, v46
	v_mul_f32_e32 v86, v58, v58
	v_mul_f32_e32 v88, v59, v59
	v_mul_f32_e32 v82, v72, v72
	v_mul_f32_e32 v84, v73, v73
	v_pk_add_f32 v[86:87], v[86:87], v[88:89]
	v_pk_add_f32 v[82:83], v[82:83], v[84:85]
	s_nop 0
	v_pk_add_f32 v[82:83], v[86:87], v[82:83]
	s_nop 0
	v_add_f32_e32 v34, v82, v83
	s_nop 1
	v_add_f32_dpp v34, v34, v34 quad_perm:[1,0,3,2] row_mask:0xf bank_mask:0xf bound_ctrl:1
	s_nop 1
	v_add_f32_dpp v34, v34, v34 quad_perm:[2,3,0,1] row_mask:0xf bank_mask:0xf bound_ctrl:1
	s_nop 1
	v_add_f32_dpp v34, v34, v34 row_half_mirror row_mask:0xf bank_mask:0xf bound_ctrl:1
	s_nop 1
	v_add_f32_dpp v34, v34, v34 row_mirror row_mask:0xf bank_mask:0xf bound_ctrl:1
	s_nop 0
	v_readlane_b32 s8, v34, 16
	v_readlane_b32 s9, v34, 48
	v_readlane_b32 s0, v34, 0
	v_readlane_b32 s1, v34, 32
	v_mov_b32_e32 v82, s8
	v_mov_b32_e32 v83, s9
	v_pk_add_f32 v[82:83], s[0:1], v[82:83]
	s_mov_b32 s0, 0xf800000
	v_add_f32_e32 v34, v82, v83
	v_fmamk_f32 v34, v34, 0x3a800000, v76
	v_mul_f32_e32 v46, 0x4f800000, v34
	v_cmp_gt_f32_e32 vcc, s0, v34
	s_nop 1
	v_cndmask_b32_e32 v34, v34, v46, vcc
	v_sqrt_f32_e32 v46, v34
	s_nop 0
	v_add_u32_e32 v81, -1, v46
	v_fma_f32 v82, -v81, v46, v34
	v_cmp_ge_f32_e64 s[14:15], 0, v82
	v_add_u32_e32 v82, 1, v46
	s_nop 0
	v_cndmask_b32_e64 v81, v46, v81, s[14:15]
	v_fma_f32 v46, -v82, v46, v34
	v_cmp_lt_f32_e64 s[14:15], 0, v46
	s_nop 1
	v_cndmask_b32_e64 v46, v81, v82, s[14:15]
	v_mul_f32_e32 v81, 0x37800000, v46
	v_cndmask_b32_e32 v46, v46, v81, vcc
	v_cmp_class_f32_e32 vcc, v34, v77
	s_nop 1
	v_cndmask_b32_e32 v34, v46, v34, vcc
	v_div_scale_f32 v46, s[0:1], v34, v34, 1.0
	v_rcp_f32_e32 v81, v46
	s_lshl_b64 s[0:1], s[30:31], 11
	s_sub_i32 s30, s28, s33
	s_cmp_gt_i32 s30, 0xffff
	v_fma_f32 v82, -v46, v81, 1.0
	v_fmac_f32_e32 v81, v82, v81
	v_div_scale_f32 v82, vcc, 1.0, v34, 1.0
	v_mul_f32_e32 v83, v82, v81
	v_fma_f32 v84, -v46, v83, v82
	v_fmac_f32_e32 v83, v84, v81
	v_fma_f32 v46, -v46, v83, v82
	v_div_fmas_f32 v46, v46, v81, v83
	v_div_fixup_f32 v34, v46, v34, 1.0
	v_pk_mul_f32 v[66:67], v[66:67], v[34:35] op_sel_hi:[1,0]
	v_pk_mul_f32 v[62:63], v[62:63], v[34:35] op_sel_hi:[1,0]
	v_pk_fma_f32 v[66:67], v[10:11], v[66:67], v[14:15]
	v_pk_fma_f32 v[62:63], v[12:13], v[62:63], v[16:17]
	v_cvt_pk_bf16_f32 v66, v66, v67
	v_cvt_pk_bf16_f32 v67, v62, v63
	v_pk_mul_f32 v[62:63], v[64:65], v[34:35] op_sel_hi:[1,0]
	v_pk_mul_f32 v[60:61], v[60:61], v[34:35] op_sel_hi:[1,0]
	v_pk_fma_f32 v[62:63], v[18:19], v[62:63], v[22:23]
	v_pk_fma_f32 v[60:61], v[20:21], v[60:61], v[24:25]
	v_pk_mul_f32 v[70:71], v[70:71], v[34:35] op_sel_hi:[1,0]
	v_pk_mul_f32 v[68:69], v[68:69], v[34:35] op_sel_hi:[1,0]
	v_cvt_pk_bf16_f32 v62, v62, v63
	v_cvt_pk_bf16_f32 v63, v60, v61
	v_pk_mul_f32 v[58:59], v[58:59], v[34:35] op_sel_hi:[1,0]
	v_pk_mul_f32 v[60:61], v[72:73], v[34:35] op_sel_hi:[1,0]
	v_pk_fma_f32 v[68:69], v[4:5], v[68:69], v[8:9]
	v_pk_fma_f32 v[70:71], v[2:3], v[70:71], v[6:7]
	v_pk_fma_f32 v[60:61], v[28:29], v[60:61], v[32:33]
	v_pk_fma_f32 v[58:59], v[26:27], v[58:59], v[30:31]
	v_cvt_pk_bf16_f32 v70, v70, v71
	v_cvt_pk_bf16_f32 v71, v68, v69
	v_lshl_add_u64 v[68:69], v[48:49], 0, s[0:1]
	v_cvt_pk_bf16_f32 v58, v58, v59
	v_cvt_pk_bf16_f32 v59, v60, v61
	global_store_dwordx2 v[68:69], v[62:63], off offset:1024
	global_store_dwordx2 v[68:69], v[58:59], off offset:1536
	v_mov_b32_e32 v62, v36
	v_mov_b32_e32 v63, v37
	v_mov_b32_e32 v64, v38
	v_mov_b32_e32 v65, v39
	v_mov_b32_e32 v60, v40
	v_mov_b32_e32 v61, v41
	v_mov_b32_e32 v58, v42
	v_mov_b32_e32 v59, v43
	s_waitcnt vmcnt(0) lgkmcnt(0)
	v_mov_b64_e32 v[42:43], v[50:51]
	v_mov_b64_e32 v[40:41], v[52:53]
	v_mov_b64_e32 v[38:39], v[54:55]
	v_mov_b64_e32 v[36:37], v[56:57]
	v_mov_b32_e32 v81, v75
	v_mov_b32_e32 v75, v79
	v_mov_b32_e32 v82, v35
	v_mov_b32_e32 v35, v80
	global_store_dwordx2 v[68:69], v[70:71], off
	global_store_dwordx2 v[68:69], v[66:67], off offset:512
	s_cbranch_scc1 .LBB0_2180
.LBB0_2171:
	s_add_i32 s28, s30, s94
	s_cmp_gt_i32 s28, 0xffff
	v_mov_b32_e32 v80, v35
	s_cbranch_scc1 .LBB0_2175
	s_ashr_i32 s29, s28, 31
	s_lshl_b64 s[0:1], s[28:29], 11
	v_lshl_add_u64 v[50:51], v[48:49], 0, s[0:1]
	global_load_dwordx2 v[56:57], v[50:51], off
	global_load_dwordx2 v[54:55], v[50:51], off offset:512
	global_load_dwordx2 v[52:53], v[50:51], off offset:1024
	s_nop 0
	global_load_dwordx2 v[50:51], v[50:51], off offset:1536
	v_mov_b32_e32 v79, v75
	v_mov_b32_e32 v80, v35
	s_and_saveexec_b64 s[14:15], s[12:13]
	s_cbranch_execz .LBB0_2174
	s_ashr_i32 s0, s28, 11
	s_ashr_i32 s1, s0, 31
	s_lshl_b64 s[0:1], s[0:1], 15
	v_or_b32_e32 v34, s0, v44
	s_and_b32 s0, s28, 0x7ff
	v_mov_b32_e32 v67, s1
	v_or_b32_e32 v66, s0, v34
	v_lshl_add_u64 v[68:69], v[66:67], 1, s[24:25]
	v_lshl_add_u64 v[66:67], v[66:67], 2, s[22:23]
	global_load_sshort v79, v[68:69], off
	global_load_dword v80, v[66:67], off

.LBB0_2177:
	s_add_u32 s10, s36, -1
	s_addc_u32 s11, s37, -1
	s_lshl_b32 s9, s9, 5
	s_and_b64 vcc, s[10:11], s[36:37]
	s_add_i32 s10, s9, s8
	s_ashr_i32 s11, s10, 31
	s_ashr_i32 s35, s34, 31
	s_lshl_b64 s[10:11], s[10:11], 18
	s_lshl_b64 s[34:35], s[34:35], 10
	s_add_u32 s9, s4, s10
	s_addc_u32 s11, s5, s11
	s_add_u32 s10, s9, s34
	s_addc_u32 s11, s11, s35
	s_lshl_b32 s1, s1, 5
	s_add_i32 s34, s1, s8
	s_ashr_i32 s35, s34, 31
	s_ashr_i32 s15, s14, 31
	v_lshlrev_b32_e32 v46, 2, v74
	s_lshl_b64 s[34:35], s[34:35], 18
	s_lshl_b64 s[14:15], s[14:15], 10
	v_lshl_add_u64 v[84:85], s[10:11], 0, v[46:47]
	s_add_u32 s1, s4, s34
	global_load_dword v83, v[84:85], off
	s_addc_u32 s9, s5, s35
	s_add_u32 s14, s1, s14
	s_addc_u32 s15, s9, s15
	v_lshl_add_u64 v[86:87], s[14:15], 0, v[46:47]
	global_load_dword v90, v[86:87], off
	global_load_dword v92, v[84:85], off offset:256
	global_load_dword v93, v[86:87], off offset:256
	global_load_dword v94, v[84:85], off offset:512
	global_load_dword v95, v[86:87], off offset:512
	global_load_dword v96, v[84:85], off offset:768
	global_load_dword v97, v[86:87], off offset:768
	v_mul_f32_e32 v46, s0, v78
	s_cmp_eq_u64 vcc, 0
	s_waitcnt vmcnt(0) lgkmcnt(0)
	v_cvt_pk_f32_fp8_e32 v[88:89], v90
	v_cvt_pk_f32_fp8_sdwa v[90:91], v90 src0_sel:WORD_1
	v_cvt_pk_f32_fp8_e32 v[84:85], v83
	v_cvt_pk_f32_fp8_sdwa v[86:87], v83 src0_sel:WORD_1
	v_pk_mul_f32 v[88:89], v[34:35], v[88:89] op_sel_hi:[0,1]
	v_pk_mul_f32 v[90:91], v[34:35], v[90:91] op_sel_hi:[0,1]
	v_pk_fma_f32 v[84:85], v[46:47], v[84:85], v[88:89] op_sel_hi:[0,1,1]
	v_pk_fma_f32 v[86:87], v[46:47], v[86:87], v[90:91] op_sel_hi:[0,1,1]
	v_cvt_pk_f32_fp8_e32 v[88:89], v93
	v_cvt_pk_f32_fp8_sdwa v[90:91], v93 src0_sel:WORD_1
	v_pk_add_f32 v[68:69], v[68:69], v[86:87]
	v_pk_add_f32 v[70:71], v[70:71], v[84:85]
	v_cvt_pk_f32_fp8_e32 v[84:85], v92
	v_cvt_pk_f32_fp8_sdwa v[86:87], v92 src0_sel:WORD_1
	v_pk_mul_f32 v[90:91], v[34:35], v[90:91] op_sel_hi:[0,1]
	v_pk_mul_f32 v[88:89], v[34:35], v[88:89] op_sel_hi:[0,1]
	v_pk_fma_f32 v[84:85], v[46:47], v[84:85], v[88:89] op_sel_hi:[0,1,1]
	v_pk_fma_f32 v[86:87], v[46:47], v[86:87], v[90:91] op_sel_hi:[0,1,1]
	v_cvt_pk_f32_fp8_e32 v[88:89], v95
	v_cvt_pk_f32_fp8_sdwa v[90:91], v95 src0_sel:WORD_1
	v_pk_add_f32 v[62:63], v[62:63], v[86:87]
	v_pk_add_f32 v[66:67], v[66:67], v[84:85]
	v_cvt_pk_f32_fp8_e32 v[84:85], v94
	v_cvt_pk_f32_fp8_sdwa v[86:87], v94 src0_sel:WORD_1
	v_pk_mul_f32 v[90:91], v[34:35], v[90:91] op_sel_hi:[0,1]
	v_pk_mul_f32 v[88:89], v[34:35], v[88:89] op_sel_hi:[0,1]
	v_pk_fma_f32 v[84:85], v[46:47], v[84:85], v[88:89] op_sel_hi:[0,1,1]
	v_pk_fma_f32 v[86:87], v[46:47], v[86:87], v[90:91] op_sel_hi:[0,1,1]
	v_cvt_pk_f32_fp8_e32 v[88:89], v97
	v_cvt_pk_f32_fp8_sdwa v[90:91], v97 src0_sel:WORD_1
	v_pk_add_f32 v[60:61], v[60:61], v[86:87]
	v_pk_add_f32 v[64:65], v[64:65], v[84:85]
	v_cvt_pk_f32_fp8_e32 v[84:85], v96
	v_cvt_pk_f32_fp8_sdwa v[86:87], v96 src0_sel:WORD_1
	v_pk_mul_f32 v[90:91], v[34:35], v[90:91] op_sel_hi:[0,1]
	v_pk_mul_f32 v[88:89], v[34:35], v[88:89] op_sel_hi:[0,1]
	v_pk_fma_f32 v[84:85], v[46:47], v[84:85], v[88:89] op_sel_hi:[0,1,1]
	v_pk_fma_f32 v[86:87], v[46:47], v[86:87], v[90:91] op_sel_hi:[0,1,1]
	v_pk_add_f32 v[72:73], v[72:73], v[86:87]
	v_pk_add_f32 v[58:59], v[58:59], v[84:85]
	s_cbranch_scc1 .LBB0_2170

.LBB0_2183:
	s_mul_hi_i32 s0, s21, 0x2aaaaaab
	s_lshr_b32 s1, s0, 31
	s_ashr_i32 s0, s0, 8
	s_add_i32 s12, s0, s1
	s_mul_i32 s0, s12, 0xfffffa00
	s_add_i32 s24, s21, s0
	s_lshr_b32 s0, s24, 22
	s_and_b32 s0, s0, 0x1ff
	s_add_i32 s25, s24, s0
	s_and_b32 s0, s25, 0xfe00
	s_sub_i32 s0, s24, s0
	s_sext_i32_i16 s1, s0
	s_bfe_u32 s1, s1, 0x5001a
	s_add_i32 s1, s0, s1
	s_sext_i32_i16 s10, s1
	s_and_b32 s1, s1, 0xffe0
	s_lshl_b32 s23, s10, 1
	s_sub_i32 s0, s0, s1
	s_andn2_b32 s23, s23, 63
	s_sext_i32_i16 s22, s0
	s_lshl_b32 s10, s22, 5
	v_or_b32_e32 v20, s23, v26
	s_mov_b64 s[14:15], -1
	s_cmpk_gt_i32 s24, 0x3ff
	v_ashrrev_i32_e32 v21, 31, v20
	v_or_b32_e32 v18, 8, v20
	v_or_b32_e32 v16, 16, v20
	v_or_b32_e32 v14, 24, v20
	v_or_b32_e32 v12, 32, v20
	v_or_b32_e32 v10, 40, v20
	v_or_b32_e32 v8, 48, v20
	v_or_b32_e32 v6, 56, v20
	s_cbranch_scc0 .LBB0_2185
	s_ashr_i32 s13, s12, 31
	s_lshl_b64 s[0:1], s[12:13], 20
	s_lshl_b64 s[14:15], s[12:13], 22
	s_add_u32 s13, s8, s14
	s_addc_u32 s14, s9, s15
	s_add_u32 s15, s6, s0
	s_addc_u32 s26, s7, s1
	s_ashr_i32 s11, s10, 31
	s_lshl_b64 s[0:1], s[10:11], 2
	s_add_u32 s0, s13, s0
	s_addc_u32 s1, s14, s1
	v_lshl_add_u64 v[72:73], s[0:1], 0, v[2:3]
	v_lshlrev_b64 v[22:23], 12, v[20:21]
	v_lshl_add_u64 v[22:23], v[72:73], 0, v[22:23]
	v_ashrrev_i32_e32 v19, 31, v18
	global_load_dwordx4 v[22:25], v[22:23], off nt
	v_lshlrev_b64 v[48:49], 12, v[18:19]
	v_lshl_add_u64 v[48:49], v[72:73], 0, v[48:49]
	v_ashrrev_i32_e32 v17, 31, v16
	global_load_dwordx4 v[48:51], v[48:49], off nt
	v_lshlrev_b64 v[52:53], 12, v[16:17]
	v_lshl_add_u64 v[52:53], v[72:73], 0, v[52:53]
	v_ashrrev_i32_e32 v15, 31, v14
	global_load_dwordx4 v[52:55], v[52:53], off nt
	v_lshlrev_b64 v[56:57], 12, v[14:15]
	v_lshl_add_u64 v[56:57], v[72:73], 0, v[56:57]
	v_ashrrev_i32_e32 v13, 31, v12
	global_load_dwordx4 v[56:59], v[56:57], off nt
	v_lshlrev_b64 v[60:61], 12, v[12:13]
	v_lshl_add_u64 v[60:61], v[72:73], 0, v[60:61]
	v_ashrrev_i32_e32 v11, 31, v10
	global_load_dwordx4 v[60:63], v[60:61], off nt
	v_lshlrev_b64 v[64:65], 12, v[10:11]
	v_lshl_add_u64 v[64:65], v[72:73], 0, v[64:65]
	v_ashrrev_i32_e32 v9, 31, v8
	global_load_dwordx4 v[64:67], v[64:65], off nt
	v_lshlrev_b64 v[68:69], 12, v[8:9]
	v_lshl_add_u64 v[68:69], v[72:73], 0, v[68:69]
	v_ashrrev_i32_e32 v7, 31, v6
	global_load_dwordx4 v[68:71], v[68:69], off nt
	v_lshlrev_b64 v[74:75], 12, v[6:7]
	v_lshl_add_u64 v[72:73], v[72:73], 0, v[74:75]
	global_load_dwordx4 v[72:75], v[72:73], off nt
	s_ashr_i32 s1, s23, 31
	s_add_u32 s0, s15, s23
	s_addc_u32 s1, s26, s1
	s_waitcnt vmcnt(0)
	ds_write2_b32 v31, v22, v23 offset1:1
	ds_write2_b32 v31, v24, v25 offset0:2 offset1:3
	s_waitcnt vmcnt(6)
	ds_write2_b32 v32, v48, v49 offset1:1
	ds_write2_b32 v33, v50, v51 offset1:1
	s_waitcnt vmcnt(5)
	ds_write2_b32 v34, v52, v53 offset1:1
	ds_write2_b32 v35, v54, v55 offset1:1
	s_waitcnt vmcnt(4)
	ds_write2_b32 v36, v56, v57 offset1:1
	ds_write2_b32 v37, v58, v59 offset1:1
	s_waitcnt vmcnt(3)
	ds_write2_b32 v38, v60, v61 offset1:1
	ds_write2_b32 v39, v62, v63 offset1:1
	s_waitcnt vmcnt(2)
	ds_write2_b32 v40, v64, v65 offset1:1
	ds_write2_b32 v41, v66, v67 offset1:1
	s_waitcnt vmcnt(1)
	ds_write2_b32 v42, v68, v69 offset1:1
	ds_write2_b32 v43, v70, v71 offset1:1
	s_waitcnt vmcnt(0)
	ds_write2_b32 v44, v72, v73 offset1:1
	ds_write2_b32 v45, v74, v75 offset1:1
	s_waitcnt lgkmcnt(0)
	ds_read_b32 v7, v30
	ds_read_b32 v9, v30 offset:132
	ds_read_b32 v11, v30 offset:264
	ds_read_b32 v13, v30 offset:396
	v_mov_b32_e32 v24, v3
	s_waitcnt lgkmcnt(0)
	v_mul_f32_e32 v7, 0x43000000, v7
	s_waitcnt lgkmcnt(2)
	v_mul_f32_e32 v9, 0x43000000, v9
	v_med3_f32 v7, v7, s20, v46
	v_med3_f32 v9, v9, s20, v46
	v_cvt_pk_fp8_f32 v24, v7, v9
	s_waitcnt lgkmcnt(1)
	v_mul_f32_e32 v11, 0x43000000, v11
	s_waitcnt lgkmcnt(0)
	v_mul_f32_e32 v13, 0x43000000, v13
	v_med3_f32 v7, v11, s20, v46
	v_med3_f32 v9, v13, s20, v46
	v_cvt_pk_fp8_f32 v24, v7, v9 op_sel:[0,0,1]
	ds_read_b32 v7, v30 offset:528
	ds_read_b32 v9, v30 offset:660
	ds_read_b32 v11, v30 offset:792
	ds_read_b32 v13, v30 offset:924
	v_mov_b32_e32 v25, v3
	s_waitcnt lgkmcnt(3)
	v_mul_f32_e32 v7, 0x43000000, v7
	s_waitcnt lgkmcnt(2)
	v_mul_f32_e32 v9, 0x43000000, v9
	v_med3_f32 v7, v7, s20, v46
	v_med3_f32 v9, v9, s20, v46
	v_cvt_pk_fp8_f32 v25, v7, v9
	s_waitcnt lgkmcnt(1)
	v_mul_f32_e32 v11, 0x43000000, v11
	s_waitcnt lgkmcnt(0)
	v_mul_f32_e32 v13, 0x43000000, v13
	v_med3_f32 v7, v11, s20, v46
	v_med3_f32 v9, v13, s20, v46
	v_cvt_pk_fp8_f32 v25, v7, v9 op_sel:[0,0,1]
	v_or_b32_e32 v48, s10, v26
	v_ashrrev_i32_e32 v49, 31, v48
	v_lshl_add_u64 v[22:23], s[0:1], 0, v[4:5]
	v_lshlrev_b64 v[48:49], 10, v[48:49]
	v_lshl_add_u64 v[48:49], v[22:23], 0, v[48:49]
	global_store_dwordx2 v[48:49], v[24:25], off
	ds_read_b32 v7, v30 offset:32
	ds_read_b32 v9, v30 offset:164
	ds_read_b32 v11, v30 offset:296
	ds_read_b32 v13, v30 offset:428
	v_mov_b32_e32 v24, v3
	s_waitcnt lgkmcnt(0)
	v_mul_f32_e32 v7, 0x43000000, v7
	v_mul_f32_e32 v9, 0x43000000, v9
	v_med3_f32 v7, v7, s20, v46
	v_med3_f32 v9, v9, s20, v46
	v_cvt_pk_fp8_f32 v24, v7, v9
	v_mul_f32_e32 v11, 0x43000000, v11
	v_mul_f32_e32 v13, 0x43000000, v13
	v_med3_f32 v7, v11, s20, v46
	v_med3_f32 v9, v13, s20, v46
	v_cvt_pk_fp8_f32 v24, v7, v9 op_sel:[0,0,1]
	ds_read_b32 v7, v30 offset:560
	ds_read_b32 v9, v30 offset:692
	ds_read_b32 v11, v30 offset:824
	ds_read_b32 v13, v30 offset:956
	v_mov_b32_e32 v25, v3
	s_waitcnt lgkmcnt(0)
	v_mul_f32_e32 v7, 0x43000000, v7
	v_mul_f32_e32 v9, 0x43000000, v9
	v_med3_f32 v7, v7, s20, v46
	v_med3_f32 v9, v9, s20, v46
	v_cvt_pk_fp8_f32 v25, v7, v9
	v_mul_f32_e32 v11, 0x43000000, v11
	v_mul_f32_e32 v13, 0x43000000, v13
	v_med3_f32 v7, v11, s20, v46
	v_med3_f32 v9, v13, s20, v46
	v_cvt_pk_fp8_f32 v25, v7, v9 op_sel:[0,0,1]
	v_or_b32_e32 v48, s10, v27
	v_ashrrev_i32_e32 v49, 31, v48
	v_lshlrev_b64 v[48:49], 10, v[48:49]
	v_lshl_add_u64 v[48:49], v[22:23], 0, v[48:49]
	global_store_dwordx2 v[48:49], v[24:25], off
	ds_read_b32 v7, v30 offset:64
	ds_read_b32 v9, v30 offset:196
	ds_read_b32 v11, v30 offset:328
	ds_read_b32 v13, v30 offset:460
	v_mov_b32_e32 v24, v3
	s_waitcnt lgkmcnt(0)
	v_mul_f32_e32 v7, 0x43000000, v7
	v_mul_f32_e32 v9, 0x43000000, v9
	v_med3_f32 v7, v7, s20, v46
	v_med3_f32 v9, v9, s20, v46
	v_cvt_pk_fp8_f32 v24, v7, v9
	v_mul_f32_e32 v11, 0x43000000, v11
	v_mul_f32_e32 v13, 0x43000000, v13
	v_med3_f32 v7, v11, s20, v46
	v_med3_f32 v9, v13, s20, v46
	v_cvt_pk_fp8_f32 v24, v7, v9 op_sel:[0,0,1]
	ds_read_b32 v7, v30 offset:592
	ds_read_b32 v9, v30 offset:724
	ds_read_b32 v11, v30 offset:856
	ds_read_b32 v13, v30 offset:988
	v_mov_b32_e32 v25, v3
	s_waitcnt lgkmcnt(0)
	v_mul_f32_e32 v7, 0x43000000, v7
	v_mul_f32_e32 v9, 0x43000000, v9
	v_med3_f32 v7, v7, s20, v46
	v_med3_f32 v9, v9, s20, v46
	v_cvt_pk_fp8_f32 v25, v7, v9
	v_mul_f32_e32 v11, 0x43000000, v11
	v_mul_f32_e32 v13, 0x43000000, v13
	v_med3_f32 v7, v11, s20, v46
	v_med3_f32 v9, v13, s20, v46
	v_cvt_pk_fp8_f32 v25, v7, v9 op_sel:[0,0,1]
	v_or_b32_e32 v48, s10, v28
	v_ashrrev_i32_e32 v49, 31, v48
	v_lshlrev_b64 v[48:49], 10, v[48:49]
	v_lshl_add_u64 v[48:49], v[22:23], 0, v[48:49]
	global_store_dwordx2 v[48:49], v[24:25], off
	ds_read_b32 v7, v30 offset:96
	ds_read_b32 v9, v30 offset:228
	ds_read_b32 v11, v30 offset:360
	ds_read_b32 v13, v30 offset:492
	v_mov_b32_e32 v24, v3
	s_waitcnt lgkmcnt(0)
	v_mul_f32_e32 v7, 0x43000000, v7
	v_mul_f32_e32 v9, 0x43000000, v9
	v_med3_f32 v7, v7, s20, v46
	v_med3_f32 v9, v9, s20, v46
	v_cvt_pk_fp8_f32 v24, v7, v9
	v_mul_f32_e32 v11, 0x43000000, v11
	v_mul_f32_e32 v13, 0x43000000, v13
	v_med3_f32 v7, v11, s20, v46
	v_med3_f32 v9, v13, s20, v46
	v_cvt_pk_fp8_f32 v24, v7, v9 op_sel:[0,0,1]
	ds_read_b32 v7, v30 offset:624
	ds_read_b32 v9, v30 offset:756
	ds_read_b32 v11, v30 offset:888
	ds_read_b32 v13, v30 offset:1020
	v_mov_b32_e32 v25, v3
	s_waitcnt lgkmcnt(0)
	v_mul_f32_e32 v7, 0x43000000, v7
	v_mul_f32_e32 v9, 0x43000000, v9
	v_med3_f32 v7, v7, s20, v46
	v_med3_f32 v9, v9, s20, v46
	v_cvt_pk_fp8_f32 v25, v7, v9
	v_mul_f32_e32 v11, 0x43000000, v11
	v_mul_f32_e32 v13, 0x43000000, v13
	v_med3_f32 v7, v11, s20, v46
	v_med3_f32 v9, v13, s20, v46
	v_cvt_pk_fp8_f32 v25, v7, v9 op_sel:[0,0,1]
	v_or_b32_e32 v48, s10, v29
	v_ashrrev_i32_e32 v49, 31, v48
	v_lshlrev_b64 v[48:49], 10, v[48:49]
	v_lshl_add_u64 v[22:23], v[22:23], 0, v[48:49]
	global_store_dwordx2 v[22:23], v[24:25], off
	s_waitcnt lgkmcnt(0)
	s_cbranch_execnz .LBB0_2182
	s_branch .LBB0_2186

.LBB0_2186:
	s_sext_i32_i16 s0, s25
	s_lshr_b32 s0, s0, 9
	s_addk_i32 s24, 0x1ff
	s_cmpk_lt_u32 s24, 0x3ff
	s_cselect_b32 s11, s17, s19
	s_cselect_b32 s15, s16, s18
	s_ashr_i32 s13, s12, 31
	s_sext_i32_i16 s14, s0
	s_lshl_b64 s[0:1], s[12:13], 22
	s_add_u32 s15, s15, s0
	s_addc_u32 s24, s11, s1
	s_lshl_b64 s[0:1], s[12:13], 21
	s_add_u32 s12, s4, s0
	s_addc_u32 s13, s5, s1
	s_ashr_i32 s11, s10, 31
	s_lshl_b64 s[0:1], s[10:11], 2
	s_add_u32 s0, s15, s0
	s_addc_u32 s1, s24, s1
	v_lshl_add_u64 v[22:23], s[0:1], 0, v[2:3]
	s_mov_b64 s[0:1], 0xc000000
	v_lshl_add_u64 v[24:25], v[22:23], 0, s[0:1]
	v_lshlrev_b64 v[20:21], 12, v[20:21]
	v_lshl_add_u64 v[20:21], v[24:25], 0, v[20:21]
	v_ashrrev_i32_e32 v19, 31, v18
	global_load_dwordx4 v[20:23], v[20:21], off nt
	v_lshlrev_b64 v[18:19], 12, v[18:19]
	v_lshl_add_u64 v[18:19], v[24:25], 0, v[18:19]
	v_ashrrev_i32_e32 v17, 31, v16
	global_load_dwordx4 v[48:51], v[18:19], off nt
	v_lshlrev_b64 v[16:17], 12, v[16:17]
	v_lshl_add_u64 v[16:17], v[24:25], 0, v[16:17]
	v_ashrrev_i32_e32 v15, 31, v14
	global_load_dwordx4 v[16:19], v[16:17], off nt
	v_lshlrev_b64 v[14:15], 12, v[14:15]
	v_lshl_add_u64 v[14:15], v[24:25], 0, v[14:15]
	v_ashrrev_i32_e32 v13, 31, v12
	global_load_dwordx4 v[52:55], v[14:15], off nt
	v_lshlrev_b64 v[12:13], 12, v[12:13]
	v_lshl_add_u64 v[12:13], v[24:25], 0, v[12:13]
	v_ashrrev_i32_e32 v11, 31, v10
	global_load_dwordx4 v[12:15], v[12:13], off nt
	v_lshlrev_b64 v[10:11], 12, v[10:11]
	v_lshl_add_u64 v[10:11], v[24:25], 0, v[10:11]
	v_ashrrev_i32_e32 v9, 31, v8
	global_load_dwordx4 v[56:59], v[10:11], off nt
	v_lshlrev_b64 v[8:9], 12, v[8:9]
	v_lshl_add_u64 v[8:9], v[24:25], 0, v[8:9]
	v_ashrrev_i32_e32 v7, 31, v6
	global_load_dwordx4 v[8:11], v[8:9], off nt
	v_lshlrev_b64 v[6:7], 12, v[6:7]
	v_lshl_add_u64 v[6:7], v[24:25], 0, v[6:7]
	global_load_dwordx4 v[60:63], v[6:7], off nt
	s_lshl_b32 s1, s14, 7
	s_ashr_i32 s0, s23, 31
	s_add_u32 s12, s12, s23
	s_addc_u32 s13, s13, s0
	s_lshl_b32 s0, s22, 6
	s_and_b32 s0, s0, 0xffffff00
	s_add_i32 s0, s0, s1
	s_and_b32 s1, s10, 0x60
	s_or_b32 s10, s0, s1
	v_lshl_add_u64 v[6:7], s[12:13], 0, v[4:5]
	s_waitcnt vmcnt(0)
	ds_write2_b32 v31, v20, v21 offset1:1
	ds_write2_b32 v31, v22, v23 offset0:2 offset1:3
	ds_write2_b32 v32, v48, v49 offset1:1
	ds_write2_b32 v33, v50, v51 offset1:1
	ds_write2_b32 v34, v16, v17 offset1:1
	ds_write2_b32 v35, v18, v19 offset1:1
	ds_write2_b32 v36, v52, v53 offset1:1
	ds_write2_b32 v37, v54, v55 offset1:1
	ds_write2_b32 v38, v12, v13 offset1:1
	ds_write2_b32 v39, v14, v15 offset1:1
	ds_write2_b32 v40, v56, v57 offset1:1
	ds_write2_b32 v41, v58, v59 offset1:1
	ds_write2_b32 v42, v8, v9 offset1:1
	ds_write2_b32 v43, v10, v11 offset1:1
	ds_write2_b32 v44, v60, v61 offset1:1
	ds_write2_b32 v45, v62, v63 offset1:1
	s_waitcnt lgkmcnt(0)
	ds_read_b32 v8, v30
	ds_read_b32 v9, v30 offset:132
	ds_read_b32 v10, v30 offset:264
	ds_read_b32 v11, v30 offset:396
	s_waitcnt lgkmcnt(0)
	v_mul_f32_e32 v8, 0x42800000, v8
	v_mul_f32_e32 v9, 0x42800000, v9
	v_med3_f32 v12, v8, s20, v46
	v_med3_f32 v9, v9, s20, v46
	v_mov_b32_e32 v8, v3
	v_cvt_pk_fp8_f32 v8, v12, v9
	v_mul_f32_e32 v10, 0x42800000, v10
	v_mul_f32_e32 v11, 0x42800000, v11
	v_med3_f32 v9, v10, s20, v46
	v_med3_f32 v10, v11, s20, v46
	v_cvt_pk_fp8_f32 v8, v9, v10 op_sel:[0,0,1]
	ds_read_b32 v9, v30 offset:528
	ds_read_b32 v10, v30 offset:660
	ds_read_b32 v11, v30 offset:792
	ds_read_b32 v12, v30 offset:924
	s_waitcnt lgkmcnt(3)
	v_mul_f32_e32 v9, 0x42800000, v9
	s_waitcnt lgkmcnt(2)
	v_mul_f32_e32 v10, 0x42800000, v10
	v_med3_f32 v13, v9, s20, v46
	v_med3_f32 v10, v10, s20, v46
	v_mov_b32_e32 v9, v3
	v_cvt_pk_fp8_f32 v9, v13, v10
	s_waitcnt lgkmcnt(1)
	v_mul_f32_e32 v11, 0x42800000, v11
	s_waitcnt lgkmcnt(0)
	v_mul_f32_e32 v12, 0x42800000, v12
	v_med3_f32 v10, v11, s20, v46
	v_med3_f32 v11, v12, s20, v46
	v_cvt_pk_fp8_f32 v9, v10, v11 op_sel:[0,0,1]
	v_or_b32_e32 v10, s10, v26
	v_ashrrev_i32_e32 v11, 31, v10
	v_lshlrev_b64 v[10:11], 10, v[10:11]
	v_lshl_add_u64 v[10:11], v[6:7], 0, v[10:11]
	global_store_dwordx2 v[10:11], v[8:9], off
	ds_read_b32 v8, v30 offset:32
	ds_read_b32 v9, v30 offset:164
	ds_read_b32 v10, v30 offset:296
	ds_read_b32 v11, v30 offset:428
	s_waitcnt lgkmcnt(0)
	v_mul_f32_e32 v8, 0x42800000, v8
	v_mul_f32_e32 v9, 0x42800000, v9
	v_med3_f32 v12, v8, s20, v46
	v_med3_f32 v9, v9, s20, v46
	v_mov_b32_e32 v8, v3
	v_cvt_pk_fp8_f32 v8, v12, v9
	v_mul_f32_e32 v10, 0x42800000, v10
	v_mul_f32_e32 v11, 0x42800000, v11
	v_med3_f32 v9, v10, s20, v46
	v_med3_f32 v10, v11, s20, v46
	v_cvt_pk_fp8_f32 v8, v9, v10 op_sel:[0,0,1]
	ds_read_b32 v9, v30 offset:560
	ds_read_b32 v10, v30 offset:692
	ds_read_b32 v11, v30 offset:824
	ds_read_b32 v12, v30 offset:956
	s_waitcnt lgkmcnt(0)
	v_mul_f32_e32 v9, 0x42800000, v9
	v_mul_f32_e32 v10, 0x42800000, v10
	v_med3_f32 v13, v9, s20, v46
	v_med3_f32 v10, v10, s20, v46
	v_mov_b32_e32 v9, v3
	v_cvt_pk_fp8_f32 v9, v13, v10
	v_mul_f32_e32 v11, 0x42800000, v11
	v_mul_f32_e32 v12, 0x42800000, v12
	v_med3_f32 v10, v11, s20, v46
	v_med3_f32 v11, v12, s20, v46
	v_cvt_pk_fp8_f32 v9, v10, v11 op_sel:[0,0,1]
	v_or_b32_e32 v10, s10, v27
	v_ashrrev_i32_e32 v11, 31, v10
	v_lshlrev_b64 v[10:11], 10, v[10:11]
	v_lshl_add_u64 v[10:11], v[6:7], 0, v[10:11]
	global_store_dwordx2 v[10:11], v[8:9], off
	ds_read_b32 v8, v30 offset:64
	ds_read_b32 v9, v30 offset:196
	ds_read_b32 v10, v30 offset:328
	ds_read_b32 v11, v30 offset:460
	s_waitcnt lgkmcnt(0)
	v_mul_f32_e32 v8, 0x42800000, v8
	v_mul_f32_e32 v9, 0x42800000, v9
	v_med3_f32 v12, v8, s20, v46
	v_med3_f32 v9, v9, s20, v46
	v_mov_b32_e32 v8, v3
	v_cvt_pk_fp8_f32 v8, v12, v9
	v_mul_f32_e32 v10, 0x42800000, v10
	v_mul_f32_e32 v11, 0x42800000, v11
	v_med3_f32 v9, v10, s20, v46
	v_med3_f32 v10, v11, s20, v46
	v_cvt_pk_fp8_f32 v8, v9, v10 op_sel:[0,0,1]
	ds_read_b32 v9, v30 offset:592
	ds_read_b32 v10, v30 offset:724
	ds_read_b32 v11, v30 offset:856
	ds_read_b32 v12, v30 offset:988
	s_waitcnt lgkmcnt(0)
	v_mul_f32_e32 v9, 0x42800000, v9
	v_mul_f32_e32 v10, 0x42800000, v10
	v_med3_f32 v13, v9, s20, v46
	v_med3_f32 v10, v10, s20, v46
	v_mov_b32_e32 v9, v3
	v_cvt_pk_fp8_f32 v9, v13, v10
	v_mul_f32_e32 v11, 0x42800000, v11
	v_mul_f32_e32 v12, 0x42800000, v12
	v_med3_f32 v10, v11, s20, v46
	v_med3_f32 v11, v12, s20, v46
	v_cvt_pk_fp8_f32 v9, v10, v11 op_sel:[0,0,1]
	v_or_b32_e32 v10, s10, v28
	v_ashrrev_i32_e32 v11, 31, v10
	v_lshlrev_b64 v[10:11], 10, v[10:11]
	v_lshl_add_u64 v[10:11], v[6:7], 0, v[10:11]
	global_store_dwordx2 v[10:11], v[8:9], off
	ds_read_b32 v8, v30 offset:96
	ds_read_b32 v9, v30 offset:228
	ds_read_b32 v10, v30 offset:360
	ds_read_b32 v11, v30 offset:492
	s_waitcnt lgkmcnt(0)
	v_mul_f32_e32 v8, 0x42800000, v8
	v_mul_f32_e32 v9, 0x42800000, v9
	v_med3_f32 v12, v8, s20, v46
	v_med3_f32 v9, v9, s20, v46
	v_mov_b32_e32 v8, v3
	v_cvt_pk_fp8_f32 v8, v12, v9
	v_mul_f32_e32 v10, 0x42800000, v10
	v_mul_f32_e32 v11, 0x42800000, v11
	v_med3_f32 v9, v10, s20, v46
	v_med3_f32 v10, v11, s20, v46
	v_cvt_pk_fp8_f32 v8, v9, v10 op_sel:[0,0,1]
	ds_read_b32 v9, v30 offset:624
	ds_read_b32 v10, v30 offset:756
	ds_read_b32 v11, v30 offset:888
	ds_read_b32 v12, v30 offset:1020
	s_waitcnt lgkmcnt(0)
	v_mul_f32_e32 v9, 0x42800000, v9
	v_mul_f32_e32 v10, 0x42800000, v10
	v_med3_f32 v13, v9, s20, v46
	v_med3_f32 v10, v10, s20, v46
	v_mov_b32_e32 v9, v3
	v_cvt_pk_fp8_f32 v9, v13, v10
	v_mul_f32_e32 v11, 0x42800000, v11
	v_mul_f32_e32 v12, 0x42800000, v12
	v_med3_f32 v10, v11, s20, v46
	v_med3_f32 v11, v12, s20, v46
	v_cvt_pk_fp8_f32 v9, v10, v11 op_sel:[0,0,1]
	v_or_b32_e32 v10, s10, v29
	v_ashrrev_i32_e32 v11, 31, v10
	v_lshlrev_b64 v[10:11], 10, v[10:11]
	v_lshl_add_u64 v[6:7], v[6:7], 0, v[10:11]
	global_store_dwordx2 v[6:7], v[8:9], off
	s_waitcnt lgkmcnt(0)
	s_branch .LBB0_2182

.LBB0_2245:
	ds_read_b128 v[150:153], v146
	ds_read_b128 v[154:157], v146 offset:1024
	ds_read_b128 v[158:161], v146 offset:2048
	ds_read_b128 v[162:165], v146 offset:3072
	s_add_u32 s0, s30, 0xfffc0080
	s_addc_u32 s1, s31, -1
	s_cmp_eq_u32 s61, 12
	s_cselect_b32 s37, s55, s1
	s_cselect_b32 s36, s56, s0
	s_cselect_b32 s35, s57, s60
	s_cselect_b32 s34, s58, s59
	s_mov_b32 m0, s46
	v_lshl_add_u64 v[198:199], s[30:31], 0, v[140:141]
	ds_read_b128 v[166:169], v147
	ds_read_b128 v[170:173], v147 offset:1024
	ds_read_b128 v[174:177], v147 offset:2048
	ds_read_b128 v[178:181], v147 offset:3072
	ds_read_b128 v[182:185], v147 offset:4096
	ds_read_b128 v[186:189], v147 offset:5120
	ds_read_b128 v[190:193], v147 offset:6144
	ds_read_b128 v[194:197], v147 offset:7168
	global_load_lds_dwordx4 v[198:199], off
	v_lshl_add_u64 v[198:199], s[30:31], 0, v[138:139]
	s_mov_b32 m0, s47
	s_nop 0
	global_load_lds_dwordx4 v[198:199], off
	s_waitcnt lgkmcnt(8)
	s_waitcnt vmcnt(10)
	s_barrier
	s_waitcnt lgkmcnt(0)
	s_waitcnt lgkmcnt(0)
	v_mfma_f32_16x16x32_bf16 v[126:129], v[150:153], v[166:169], v[126:129]
	v_mfma_f32_16x16x32_bf16 v[122:125], v[158:161], v[166:169], v[122:125]
	v_mfma_f32_16x16x32_bf16 v[118:121], v[150:153], v[174:177], v[118:121]
	v_mfma_f32_16x16x32_bf16 v[114:117], v[158:161], v[174:177], v[114:117]
	v_mfma_f32_16x16x32_bf16 v[102:105], v[150:153], v[182:185], v[102:105]
	v_mfma_f32_16x16x32_bf16 v[98:101], v[158:161], v[182:185], v[98:101]
	v_mfma_f32_16x16x32_bf16 v[86:89], v[150:153], v[190:193], v[86:89]
	v_mfma_f32_16x16x32_bf16 v[82:85], v[158:161], v[190:193], v[82:85]
	v_mfma_f32_16x16x32_bf16 v[126:129], v[154:157], v[170:173], v[126:129]
	v_mfma_f32_16x16x32_bf16 v[122:125], v[162:165], v[170:173], v[122:125]
	v_mfma_f32_16x16x32_bf16 v[118:121], v[154:157], v[178:181], v[118:121]
	v_mfma_f32_16x16x32_bf16 v[114:117], v[162:165], v[178:181], v[114:117]
	v_mfma_f32_16x16x32_bf16 v[102:105], v[154:157], v[186:189], v[102:105]
	v_mfma_f32_16x16x32_bf16 v[98:101], v[162:165], v[186:189], v[98:101]
	v_mfma_f32_16x16x32_bf16 v[86:89], v[154:157], v[194:197], v[86:89]
	v_mfma_f32_16x16x32_bf16 v[82:85], v[162:165], v[194:197], v[82:85]
	s_barrier
	s_mov_b32 m0, s48
	v_lshl_add_u64 v[214:215], s[34:35], 0, v[134:135]
	ds_read_b128 v[198:201], v148
	ds_read_b128 v[202:205], v148 offset:1024
	ds_read_b128 v[206:209], v148 offset:2048
	ds_read_b128 v[210:213], v148 offset:3072
	global_load_lds_dwordx4 v[214:215], off
	v_lshl_add_u64 v[216:217], s[34:35], 0, v[130:131]
	s_mov_b32 m0, s49
	s_nop 0
	global_load_lds_dwordx4 v[216:217], off
	s_waitcnt vmcnt(10)
	s_barrier
	s_waitcnt lgkmcnt(0)
	s_waitcnt lgkmcnt(0)
	v_mfma_f32_16x16x32_bf16 v[110:113], v[198:201], v[166:169], v[110:113]
	v_mfma_f32_16x16x32_bf16 v[106:109], v[206:209], v[166:169], v[106:109]
	v_mfma_f32_16x16x32_bf16 v[94:97], v[198:201], v[174:177], v[94:97]
	v_mfma_f32_16x16x32_bf16 v[90:93], v[206:209], v[174:177], v[90:93]
	v_mfma_f32_16x16x32_bf16 v[78:81], v[198:201], v[182:185], v[78:81]
	v_mfma_f32_16x16x32_bf16 v[74:77], v[206:209], v[182:185], v[74:77]
	v_mfma_f32_16x16x32_bf16 v[70:73], v[198:201], v[190:193], v[70:73]
	v_mfma_f32_16x16x32_bf16 v[66:69], v[206:209], v[190:193], v[66:69]
	v_mfma_f32_16x16x32_bf16 v[110:113], v[202:205], v[170:173], v[110:113]
	v_mfma_f32_16x16x32_bf16 v[106:109], v[210:213], v[170:173], v[106:109]
	v_mfma_f32_16x16x32_bf16 v[94:97], v[202:205], v[178:181], v[94:97]
	v_mfma_f32_16x16x32_bf16 v[90:93], v[210:213], v[178:181], v[90:93]
	v_mfma_f32_16x16x32_bf16 v[78:81], v[202:205], v[186:189], v[78:81]
	v_mfma_f32_16x16x32_bf16 v[74:77], v[210:213], v[186:189], v[74:77]
	v_mfma_f32_16x16x32_bf16 v[70:73], v[202:205], v[194:197], v[70:73]
	v_mfma_f32_16x16x32_bf16 v[66:69], v[210:213], v[194:197], v[66:69]
	s_mov_b32 m0, s9
	v_lshl_add_u64 v[218:219], s[36:37], 0, v[136:137]
	s_barrier
	ds_read_b128 v[166:169], v147 offset:16384
	ds_read_b128 v[170:173], v147 offset:17408
	ds_read_b128 v[174:177], v147 offset:18432
	ds_read_b128 v[178:181], v147 offset:19456
	ds_read_b128 v[182:185], v147 offset:20480
	ds_read_b128 v[186:189], v147 offset:21504
	ds_read_b128 v[190:193], v147 offset:22528
	ds_read_b128 v[194:197], v147 offset:23552
	global_load_lds_dwordx4 v[218:219], off
	v_lshl_add_u64 v[220:221], s[36:37], 0, v[132:133]
	s_mov_b32 m0, s21
	s_nop 0
	global_load_lds_dwordx4 v[220:221], off
	s_waitcnt vmcnt(10)
	s_barrier
	s_waitcnt lgkmcnt(0)
	s_waitcnt lgkmcnt(0)
	v_mfma_f32_16x16x32_bf16 v[62:65], v[150:153], v[166:169], v[62:65]
	v_mfma_f32_16x16x32_bf16 v[58:61], v[158:161], v[166:169], v[58:61]
	v_mfma_f32_16x16x32_bf16 v[54:57], v[150:153], v[174:177], v[54:57]
	v_mfma_f32_16x16x32_bf16 v[50:53], v[158:161], v[174:177], v[50:53]
	v_mfma_f32_16x16x32_bf16 v[38:41], v[150:153], v[182:185], v[38:41]
	v_mfma_f32_16x16x32_bf16 v[34:37], v[158:161], v[182:185], v[34:37]
	v_mfma_f32_16x16x32_bf16 v[22:25], v[150:153], v[190:193], v[22:25]
	v_mfma_f32_16x16x32_bf16 v[18:21], v[158:161], v[190:193], v[18:21]
	v_mfma_f32_16x16x32_bf16 v[62:65], v[154:157], v[170:173], v[62:65]
	v_mfma_f32_16x16x32_bf16 v[58:61], v[162:165], v[170:173], v[58:61]
	v_mfma_f32_16x16x32_bf16 v[54:57], v[154:157], v[178:181], v[54:57]
	v_mfma_f32_16x16x32_bf16 v[50:53], v[162:165], v[178:181], v[50:53]
	v_mfma_f32_16x16x32_bf16 v[38:41], v[154:157], v[186:189], v[38:41]
	v_mfma_f32_16x16x32_bf16 v[34:37], v[162:165], v[186:189], v[34:37]
	v_mfma_f32_16x16x32_bf16 v[22:25], v[154:157], v[194:197], v[22:25]
	v_mfma_f32_16x16x32_bf16 v[18:21], v[162:165], v[194:197], v[18:21]
	s_barrier
	s_add_u32 s0, s34, 0x40000
	s_addc_u32 s1, s35, 0
	s_add_i32 s62, s44, s8
	v_lshl_add_u64 v[150:151], s[0:1], 0, v[134:135]
	s_mov_b32 m0, s62
	s_nop 0
	global_load_lds_dwordx4 v[150:151], off
	v_lshl_add_u64 v[150:151], s[0:1], 0, v[130:131]
	s_add_i32 m0, s62, 0x2000
	s_nop 0
	global_load_lds_dwordx4 v[150:151], off
	s_waitcnt vmcnt(10)
	s_barrier
	v_mfma_f32_16x16x32_bf16 v[46:49], v[198:201], v[166:169], v[46:49]
	v_mfma_f32_16x16x32_bf16 v[42:45], v[206:209], v[166:169], v[42:45]
	v_mfma_f32_16x16x32_bf16 v[30:33], v[198:201], v[174:177], v[30:33]
	v_mfma_f32_16x16x32_bf16 v[26:29], v[206:209], v[174:177], v[26:29]
	v_mfma_f32_16x16x32_bf16 v[14:17], v[198:201], v[182:185], v[14:17]
	v_mfma_f32_16x16x32_bf16 v[10:13], v[206:209], v[182:185], v[10:13]
	v_mfma_f32_16x16x32_bf16 v[6:9], v[198:201], v[190:193], v[6:9]
	v_mfma_f32_16x16x32_bf16 v[2:5], v[206:209], v[190:193], v[2:5]
	v_mfma_f32_16x16x32_bf16 v[46:49], v[202:205], v[170:173], v[46:49]
	v_mfma_f32_16x16x32_bf16 v[42:45], v[210:213], v[170:173], v[42:45]
	v_mfma_f32_16x16x32_bf16 v[30:33], v[202:205], v[178:181], v[30:33]
	v_mfma_f32_16x16x32_bf16 v[26:29], v[210:213], v[178:181], v[26:29]
	v_mfma_f32_16x16x32_bf16 v[14:17], v[202:205], v[186:189], v[14:17]
	v_mfma_f32_16x16x32_bf16 v[10:13], v[210:213], v[186:189], v[10:13]
	v_mfma_f32_16x16x32_bf16 v[6:9], v[202:205], v[194:197], v[6:9]
	v_mfma_f32_16x16x32_bf16 v[2:5], v[210:213], v[194:197], v[2:5]
	s_add_i32 s62, 0, 0x18000
	v_add_u32_e32 v149, s62, v145
	s_barrier
	ds_read_b128 v[150:153], v149
	ds_read_b128 v[154:157], v149 offset:1024
	ds_read_b128 v[158:161], v149 offset:2048
	ds_read_b128 v[162:165], v149 offset:3072
	s_add_u32 s0, s36, 0x40000
	s_addc_u32 s1, s37, 0
	s_mov_b32 m0, s38
	v_lshl_add_u64 v[198:199], s[0:1], 0, v[136:137]
	ds_read_b128 v[166:169], v147 offset:32768
	ds_read_b128 v[170:173], v147 offset:33792
	ds_read_b128 v[174:177], v147 offset:34816
	ds_read_b128 v[178:181], v147 offset:35840
	ds_read_b128 v[182:185], v147 offset:36864
	ds_read_b128 v[186:189], v147 offset:37888
	ds_read_b128 v[190:193], v147 offset:38912
	ds_read_b128 v[194:197], v147 offset:39936
	global_load_lds_dwordx4 v[198:199], off
	v_lshl_add_u64 v[198:199], s[0:1], 0, v[132:133]
	s_mov_b32 m0, s39
	s_nop 0
	global_load_lds_dwordx4 v[198:199], off
	s_waitcnt lgkmcnt(8)
	s_waitcnt vmcnt(10)
	s_barrier
	s_waitcnt lgkmcnt(0)
	s_waitcnt lgkmcnt(0)
	v_mfma_f32_16x16x32_bf16 v[126:129], v[150:153], v[166:169], v[126:129]
	v_mfma_f32_16x16x32_bf16 v[122:125], v[158:161], v[166:169], v[122:125]
	v_mfma_f32_16x16x32_bf16 v[118:121], v[150:153], v[174:177], v[118:121]
	v_mfma_f32_16x16x32_bf16 v[114:117], v[158:161], v[174:177], v[114:117]
	v_mfma_f32_16x16x32_bf16 v[102:105], v[150:153], v[182:185], v[102:105]
	v_mfma_f32_16x16x32_bf16 v[98:101], v[158:161], v[182:185], v[98:101]
	v_mfma_f32_16x16x32_bf16 v[86:89], v[150:153], v[190:193], v[86:89]
	v_mfma_f32_16x16x32_bf16 v[82:85], v[158:161], v[190:193], v[82:85]
	v_mfma_f32_16x16x32_bf16 v[126:129], v[154:157], v[170:173], v[126:129]
	v_mfma_f32_16x16x32_bf16 v[122:125], v[162:165], v[170:173], v[122:125]
	v_mfma_f32_16x16x32_bf16 v[118:121], v[154:157], v[178:181], v[118:121]
	v_mfma_f32_16x16x32_bf16 v[114:117], v[162:165], v[178:181], v[114:117]
	v_mfma_f32_16x16x32_bf16 v[102:105], v[154:157], v[186:189], v[102:105]
	v_mfma_f32_16x16x32_bf16 v[98:101], v[162:165], v[186:189], v[98:101]
	v_mfma_f32_16x16x32_bf16 v[86:89], v[154:157], v[194:197], v[86:89]
	v_mfma_f32_16x16x32_bf16 v[82:85], v[162:165], v[194:197], v[82:85]
	s_barrier
	s_add_i32 s36, 0, 0x1c000
	s_add_i32 s0, s62, s8
	v_add_u32_e32 v149, s36, v145
	v_lshl_add_u64 v[214:215], v[214:215], 0, s[24:25]
	s_mov_b32 m0, s0
	ds_read_b128 v[198:201], v149
	ds_read_b128 v[202:205], v149 offset:1024
	ds_read_b128 v[206:209], v149 offset:2048
	ds_read_b128 v[210:213], v149 offset:3072
	global_load_lds_dwordx4 v[214:215], off
	v_lshl_add_u64 v[214:215], v[216:217], 0, s[24:25]
	s_add_i32 m0, s0, 0x2000
	s_nop 0
	global_load_lds_dwordx4 v[214:215], off
	s_waitcnt vmcnt(10)
	s_barrier
	s_waitcnt lgkmcnt(0)
	s_waitcnt lgkmcnt(0)
	v_mfma_f32_16x16x32_bf16 v[110:113], v[198:201], v[166:169], v[110:113]
	v_mfma_f32_16x16x32_bf16 v[106:109], v[206:209], v[166:169], v[106:109]
	v_mfma_f32_16x16x32_bf16 v[94:97], v[198:201], v[174:177], v[94:97]
	v_mfma_f32_16x16x32_bf16 v[90:93], v[206:209], v[174:177], v[90:93]
	v_mfma_f32_16x16x32_bf16 v[78:81], v[198:201], v[182:185], v[78:81]
	v_mfma_f32_16x16x32_bf16 v[74:77], v[206:209], v[182:185], v[74:77]
	v_mfma_f32_16x16x32_bf16 v[70:73], v[198:201], v[190:193], v[70:73]
	v_mfma_f32_16x16x32_bf16 v[66:69], v[206:209], v[190:193], v[66:69]
	v_mfma_f32_16x16x32_bf16 v[110:113], v[202:205], v[170:173], v[110:113]
	v_mfma_f32_16x16x32_bf16 v[106:109], v[210:213], v[170:173], v[106:109]
	v_mfma_f32_16x16x32_bf16 v[94:97], v[202:205], v[178:181], v[94:97]
	v_mfma_f32_16x16x32_bf16 v[90:93], v[210:213], v[178:181], v[90:93]
	v_mfma_f32_16x16x32_bf16 v[78:81], v[202:205], v[186:189], v[78:81]
	v_mfma_f32_16x16x32_bf16 v[74:77], v[210:213], v[186:189], v[74:77]
	v_mfma_f32_16x16x32_bf16 v[70:73], v[202:205], v[194:197], v[70:73]
	v_mfma_f32_16x16x32_bf16 v[66:69], v[210:213], v[194:197], v[66:69]
	s_mov_b32 m0, s42
	v_lshl_add_u64 v[214:215], v[218:219], 0, s[24:25]
	s_barrier
	ds_read_b128 v[166:169], v147 offset:49152
	ds_read_b128 v[170:173], v147 offset:50176
	ds_read_b128 v[174:177], v147 offset:51200
	ds_read_b128 v[178:181], v147 offset:52224
	ds_read_b128 v[182:185], v147 offset:53248
	ds_read_b128 v[186:189], v147 offset:54272
	ds_read_b128 v[190:193], v147 offset:55296
	ds_read_b128 v[194:197], v147 offset:56320
	global_load_lds_dwordx4 v[214:215], off
	v_lshl_add_u64 v[214:215], v[220:221], 0, s[24:25]
	s_mov_b32 m0, s43
	s_nop 0
	global_load_lds_dwordx4 v[214:215], off
	s_waitcnt vmcnt(10)
	s_barrier
	s_waitcnt lgkmcnt(0)
	s_waitcnt lgkmcnt(0)
	v_mfma_f32_16x16x32_bf16 v[62:65], v[150:153], v[166:169], v[62:65]
	v_mfma_f32_16x16x32_bf16 v[58:61], v[158:161], v[166:169], v[58:61]
	v_mfma_f32_16x16x32_bf16 v[54:57], v[150:153], v[174:177], v[54:57]
	v_mfma_f32_16x16x32_bf16 v[50:53], v[158:161], v[174:177], v[50:53]
	v_mfma_f32_16x16x32_bf16 v[38:41], v[150:153], v[182:185], v[38:41]
	v_mfma_f32_16x16x32_bf16 v[34:37], v[158:161], v[182:185], v[34:37]
	v_mfma_f32_16x16x32_bf16 v[22:25], v[150:153], v[190:193], v[22:25]
	v_mfma_f32_16x16x32_bf16 v[18:21], v[158:161], v[190:193], v[18:21]
	v_mfma_f32_16x16x32_bf16 v[62:65], v[154:157], v[170:173], v[62:65]
	v_mfma_f32_16x16x32_bf16 v[58:61], v[162:165], v[170:173], v[58:61]
	v_mfma_f32_16x16x32_bf16 v[54:57], v[154:157], v[178:181], v[54:57]
	v_mfma_f32_16x16x32_bf16 v[50:53], v[162:165], v[178:181], v[50:53]
	v_mfma_f32_16x16x32_bf16 v[38:41], v[154:157], v[186:189], v[38:41]
	v_mfma_f32_16x16x32_bf16 v[34:37], v[162:165], v[186:189], v[34:37]
	v_mfma_f32_16x16x32_bf16 v[22:25], v[154:157], v[194:197], v[22:25]
	v_mfma_f32_16x16x32_bf16 v[18:21], v[162:165], v[194:197], v[18:21]
	s_barrier
	s_add_u32 s0, s34, 0x40080
	s_addc_u32 s1, s35, 0
	s_add_i32 s34, s36, s8
	v_lshl_add_u64 v[150:151], s[0:1], 0, v[134:135]
	s_mov_b32 m0, s34
	s_nop 0
	global_load_lds_dwordx4 v[150:151], off
	v_lshl_add_u64 v[150:151], s[0:1], 0, v[130:131]
	s_add_i32 m0, s34, 0x2000
	s_nop 0
	global_load_lds_dwordx4 v[150:151], off
	s_waitcnt vmcnt(10)
	s_barrier
	v_mfma_f32_16x16x32_bf16 v[46:49], v[198:201], v[166:169], v[46:49]
	v_mfma_f32_16x16x32_bf16 v[42:45], v[206:209], v[166:169], v[42:45]
	v_mfma_f32_16x16x32_bf16 v[30:33], v[198:201], v[174:177], v[30:33]
	v_mfma_f32_16x16x32_bf16 v[26:29], v[206:209], v[174:177], v[26:29]
	v_mfma_f32_16x16x32_bf16 v[14:17], v[198:201], v[182:185], v[14:17]
	v_mfma_f32_16x16x32_bf16 v[10:13], v[206:209], v[182:185], v[10:13]
	v_mfma_f32_16x16x32_bf16 v[6:9], v[198:201], v[190:193], v[6:9]
	v_mfma_f32_16x16x32_bf16 v[2:5], v[206:209], v[190:193], v[2:5]
	v_mfma_f32_16x16x32_bf16 v[46:49], v[202:205], v[170:173], v[46:49]
	v_mfma_f32_16x16x32_bf16 v[42:45], v[210:213], v[170:173], v[42:45]
	v_mfma_f32_16x16x32_bf16 v[30:33], v[202:205], v[178:181], v[30:33]
	v_mfma_f32_16x16x32_bf16 v[26:29], v[210:213], v[178:181], v[26:29]
	v_mfma_f32_16x16x32_bf16 v[14:17], v[202:205], v[186:189], v[14:17]
	v_mfma_f32_16x16x32_bf16 v[10:13], v[210:213], v[186:189], v[10:13]
	v_mfma_f32_16x16x32_bf16 v[6:9], v[202:205], v[194:197], v[6:9]
	v_mfma_f32_16x16x32_bf16 v[2:5], v[210:213], v[194:197], v[2:5]
	s_add_i32 s61, s61, 2
	s_add_u32 s59, s59, 0x100
	s_addc_u32 s60, s60, 0
	s_add_u32 s30, s30, 0x100
	s_addc_u32 s31, s31, 0
	s_cmp_gt_u32 s61, 13
	s_barrier
	s_cbranch_scc0 .LBB0_2245
	v_mov_b32_e32 v149, v143
	v_mov_b32_e32 v150, v144
	s_lshl_b32 s0, s53, 8
	s_or_b32 s0, s0, s41
	v_lshl_add_u32 v150, v150, 3, s0
	s_lshl_b32 s0, s54, 8
	s_add_i32 s0, s0, s40
	v_add_u32_e32 v149, s0, v149
	v_ashrrev_i32_e32 v151, 31, v150
	v_mov_b32_e32 v152, v149
	v_lshl_add_u64 v[150:151], v[150:151], 1, s[18:19]
	v_cvt_pk_bf16_f32 v126, v126, v127
	v_mad_i64_i32 v[152:153], s[0:1], v152, s45, v[150:151]
	v_cvt_pk_bf16_f32 v127, v128, v129
	v_cvt_pk_bf16_f32 v128, v122, v123
	v_cvt_pk_bf16_f32 v129, v124, v125
	v_cvt_pk_bf16_f32 v110, v110, v111
	v_cvt_pk_bf16_f32 v111, v112, v113
	v_cvt_pk_bf16_f32 v112, v106, v107
	v_cvt_pk_bf16_f32 v113, v108, v109
	v_add_u32_e32 v106, 16, v149
	global_store_dwordx4 v[152:153], v[126:129], off
	global_store_dwordx4 v[152:153], v[110:113], off offset:256
	v_cvt_pk_bf16_f32 v107, v120, v121
	v_cvt_pk_bf16_f32 v108, v114, v115
	v_mad_i64_i32 v[110:111], s[0:1], v106, s45, v[150:151]
	v_cvt_pk_bf16_f32 v106, v118, v119
	v_cvt_pk_bf16_f32 v109, v116, v117
	v_cvt_pk_bf16_f32 v94, v94, v95
	v_cvt_pk_bf16_f32 v95, v96, v97
	v_cvt_pk_bf16_f32 v96, v90, v91
	v_cvt_pk_bf16_f32 v97, v92, v93
	v_add_u32_e32 v90, 32, v149
	global_store_dwordx4 v[110:111], v[106:109], off
	global_store_dwordx4 v[110:111], v[94:97], off offset:256
	v_cvt_pk_bf16_f32 v91, v104, v105
	v_cvt_pk_bf16_f32 v92, v98, v99
	v_mad_i64_i32 v[94:95], s[0:1], v90, s45, v[150:151]
	v_cvt_pk_bf16_f32 v90, v102, v103
	v_cvt_pk_bf16_f32 v93, v100, v101
	v_cvt_pk_bf16_f32 v78, v78, v79
	v_cvt_pk_bf16_f32 v79, v80, v81
	v_cvt_pk_bf16_f32 v80, v74, v75
	v_cvt_pk_bf16_f32 v81, v76, v77
	v_add_u32_e32 v74, 48, v149
	global_store_dwordx4 v[94:95], v[90:93], off
	global_store_dwordx4 v[94:95], v[78:81], off offset:256
	v_cvt_pk_bf16_f32 v75, v88, v89
	v_cvt_pk_bf16_f32 v76, v82, v83
	v_mad_i64_i32 v[78:79], s[0:1], v74, s45, v[150:151]
	v_cvt_pk_bf16_f32 v74, v86, v87
	v_cvt_pk_bf16_f32 v77, v84, v85
	v_cvt_pk_bf16_f32 v70, v70, v71
	v_cvt_pk_bf16_f32 v71, v72, v73
	v_cvt_pk_bf16_f32 v72, v66, v67
	v_cvt_pk_bf16_f32 v73, v68, v69
	v_add_u32_e32 v66, 0x80, v149
	global_store_dwordx4 v[78:79], v[74:77], off
	global_store_dwordx4 v[78:79], v[70:73], off offset:256
	v_cvt_pk_bf16_f32 v62, v62, v63
	v_mad_i64_i32 v[66:67], s[0:1], v66, s45, v[150:151]
	v_cvt_pk_bf16_f32 v63, v64, v65
	v_cvt_pk_bf16_f32 v64, v58, v59
	v_cvt_pk_bf16_f32 v65, v60, v61
	v_cvt_pk_bf16_f32 v46, v46, v47
	v_cvt_pk_bf16_f32 v47, v48, v49
	v_cvt_pk_bf16_f32 v48, v42, v43
	v_cvt_pk_bf16_f32 v49, v44, v45
	v_add_u32_e32 v42, 0x90, v149
	global_store_dwordx4 v[66:67], v[62:65], off
	global_store_dwordx4 v[66:67], v[46:49], off offset:256
	v_cvt_pk_bf16_f32 v43, v56, v57
	v_cvt_pk_bf16_f32 v44, v50, v51
	v_mad_i64_i32 v[46:47], s[0:1], v42, s45, v[150:151]
	v_cvt_pk_bf16_f32 v42, v54, v55
	v_cvt_pk_bf16_f32 v45, v52, v53
	v_cvt_pk_bf16_f32 v30, v30, v31
	v_cvt_pk_bf16_f32 v31, v32, v33
	v_cvt_pk_bf16_f32 v32, v26, v27
	v_cvt_pk_bf16_f32 v33, v28, v29
	v_add_u32_e32 v26, 0xa0, v149
	global_store_dwordx4 v[46:47], v[42:45], off
	global_store_dwordx4 v[46:47], v[30:33], off offset:256
	v_cvt_pk_bf16_f32 v27, v40, v41
	v_cvt_pk_bf16_f32 v28, v34, v35
	v_mad_i64_i32 v[30:31], s[0:1], v26, s45, v[150:151]
	v_cvt_pk_bf16_f32 v26, v38, v39
	v_cvt_pk_bf16_f32 v29, v36, v37
	v_cvt_pk_bf16_f32 v14, v14, v15
	v_cvt_pk_bf16_f32 v15, v16, v17
	v_cvt_pk_bf16_f32 v16, v10, v11
	v_cvt_pk_bf16_f32 v17, v12, v13
	v_add_u32_e32 v10, 0xb0, v149
	global_store_dwordx4 v[30:31], v[26:29], off
	global_store_dwordx4 v[30:31], v[14:17], off offset:256
	v_cvt_pk_bf16_f32 v11, v24, v25
	v_cvt_pk_bf16_f32 v12, v18, v19
	v_mad_i64_i32 v[14:15], s[0:1], v10, s45, v[150:151]
	v_cvt_pk_bf16_f32 v10, v22, v23
	v_cvt_pk_bf16_f32 v13, v20, v21
	v_cvt_pk_bf16_f32 v6, v6, v7
	v_cvt_pk_bf16_f32 v7, v8, v9
	v_cvt_pk_bf16_f32 v8, v2, v3
	v_cvt_pk_bf16_f32 v9, v4, v5
	s_and_b64 vcc, exec, s[26:27]
	s_mov_b32 s53, s52
	s_mov_b32 s54, s51
	global_store_dwordx4 v[14:15], v[10:13], off
	global_store_dwordx4 v[14:15], v[6:9], off offset:256
	s_cbranch_vccz .LBB0_2244
	s_waitcnt vmcnt(0)
	s_cmpk_gt_u32 s5, 0xff
	s_cbranch_scc1 .LBB0_2249
	s_barrier

.LBB0_2253:
	s_lshl_b32 s0, s8, 8
	s_add_i32 s20, s0, s97
	s_ashr_i32 s21, s20, 31
	v_mad_i64_i32 v[14:15], s[0:1], s20, v73, v[46:47]
	s_lshl_b64 s[0:1], s[20:21], 7
	global_load_dwordx4 v[2:5], v[34:35], off
	global_load_dwordx4 v[6:9], v[36:37], off
	global_load_dwordx4 v[10:13], v[38:39], off offset:512
	global_load_dwordx2 v[32:33], v[14:15], off
	global_load_dwordx2 v[30:31], v[14:15], off offset:512
	global_load_dwordx2 v[62:63], v[14:15], off offset:1024
	v_lshl_add_u64 v[14:15], v[40:41], 0, s[0:1]
	v_lshl_add_u64 v[16:17], v[42:43], 0, s[0:1]
	global_load_dwordx4 v[22:25], v[14:15], off
	global_load_dwordx4 v[26:29], v[16:17], off
	s_mov_b32 s9, 0
	s_branch .LBB0_2255

.LBB0_2255:
	s_mov_b32 s21, s9
	s_add_i32 s9, s9, 8
	s_cmpk_eq_i32 s21, 0xf8
	s_cselect_b32 s0, s21, s9
	s_add_i32 s0, s0, s20
	s_ashr_i32 s1, s0, 31
	v_mad_i64_i32 v[14:15], s[18:19], s0, v73, v[46:47]
	s_lshl_b64 s[0:1], s[0:1], 7
	s_waitcnt vmcnt(0) lgkmcnt(0)
	v_and_b32_e32 v81, 0xffff0000, v33
	v_and_b32_e32 v80, 0xffff0000, v32
	global_load_dwordx2 v[58:59], v[14:15], off
	global_load_dwordx2 v[56:57], v[14:15], off offset:512
	global_load_dwordx2 v[54:55], v[14:15], off offset:1024
	v_lshl_add_u64 v[14:15], v[40:41], 0, s[0:1]
	v_lshl_add_u64 v[18:19], v[42:43], 0, s[0:1]
	v_lshlrev_b32_e32 v71, 16, v33
	v_lshlrev_b32_e32 v70, 16, v32
	v_pk_mul_f32 v[32:33], v[80:81], v[80:81]
	global_load_dwordx4 v[14:17], v[14:15], off
	v_pk_fma_f32 v[32:33], v[70:71], v[70:71], v[32:33]
	global_load_dwordx4 v[18:21], v[18:19], off
	v_and_b32_e32 v67, 0xffff0000, v31
	v_and_b32_e32 v66, 0xffff0000, v30
	v_add_f32_e32 v68, v32, v33
	v_lshlrev_b32_e32 v65, 16, v31
	v_lshlrev_b32_e32 v64, 16, v30
	v_pk_mul_f32 v[32:33], v[66:67], v[66:67]
	v_lshlrev_b32_e32 v60, 16, v62
	v_and_b32_e32 v61, 0xffff0000, v62
	v_lshlrev_b32_e32 v62, 16, v63
	v_and_b32_e32 v63, 0xffff0000, v63
	v_pk_fma_f32 v[32:33], v[64:65], v[64:65], v[32:33]
	v_mov_b32_e32 v30, v64
	v_add_f32_e32 v64, v32, v33
	v_mul_f32_e32 v32, v61, v61
	v_mul_f32_e32 v33, v63, v63
	v_fmac_f32_e32 v32, v60, v60
	v_fmac_f32_e32 v33, v62, v62
	v_mov_b32_e32 v31, v66
	v_add_f32_e32 v66, v32, v33
	v_cndmask_b32_e64 v32, 0, v64, s[12:13]
	v_add_f32_e32 v32, v68, v32
	v_mov_b32_e32 v82, v70
	v_mov_b32_e32 v83, v80
	v_add_f32_dpp v32, v32, v32 quad_perm:[1,0,3,2] row_mask:0xf bank_mask:0xf bound_ctrl:1
	v_mov_b32_e32 v80, v71
	s_add_i32 s22, s4, s21
	v_add_f32_dpp v32, v32, v32 quad_perm:[2,3,0,1] row_mask:0xf bank_mask:0xf bound_ctrl:1
	s_ashr_i32 s23, s22, 31
	s_nop 0
	v_add_f32_dpp v32, v32, v32 row_half_mirror row_mask:0xf bank_mask:0xf bound_ctrl:1
	s_nop 1
	v_add_f32_dpp v32, v32, v32 row_mirror row_mask:0xf bank_mask:0xf bound_ctrl:1
	s_nop 0
	v_readlane_b32 s18, v32, 16
	v_readlane_b32 s19, v32, 48
	v_readlane_b32 s0, v32, 0
	v_readlane_b32 s1, v32, 32
	v_mov_b32_e32 v32, s18
	v_mov_b32_e32 v33, s19
	v_pk_add_f32 v[32:33], s[0:1], v[32:33]
	s_nop 0
	v_add_f32_e32 v32, v32, v33
	v_cndmask_b32_e64 v33, 0, v64, s[10:11]
	v_cndmask_b32_e64 v64, 0, v66, s[12:13]
	v_add_f32_e32 v33, v33, v64
	v_fmamk_f32 v32, v32, 0x3b2aaaab, v74
	v_cmp_gt_f32_e32 vcc, s6, v32
	v_add_f32_dpp v33, v33, v33 quad_perm:[1,0,3,2] row_mask:0xf bank_mask:0xf bound_ctrl:1
	s_nop 1
	v_add_f32_dpp v33, v33, v33 quad_perm:[2,3,0,1] row_mask:0xf bank_mask:0xf bound_ctrl:1
	s_nop 1
	v_add_f32_dpp v33, v33, v33 row_half_mirror row_mask:0xf bank_mask:0xf bound_ctrl:1
	s_nop 1
	v_add_f32_dpp v33, v33, v33 row_mirror row_mask:0xf bank_mask:0xf bound_ctrl:1
	s_nop 0
	v_readlane_b32 s1, v33, 16
	v_readlane_b32 s0, v33, 0
	s_nop 0
	v_mov_b32_e32 v64, s1
	v_readlane_b32 s1, v33, 48
	v_add_f32_e32 v64, s0, v64
	v_readlane_b32 s0, v33, 32
	v_mov_b32_e32 v33, s1
	s_nop 0
	v_add_f32_e32 v33, s0, v33
	v_add_f32_e32 v33, v64, v33
	v_mul_f32_e32 v64, 0x4f800000, v32
	v_cndmask_b32_e32 v32, v32, v64, vcc
	v_sqrt_f32_e32 v64, v32
	s_nop 0
	v_add_u32_e32 v66, -1, v64
	v_fma_f32 v68, -v66, v64, v32
	v_cmp_ge_f32_e64 s[18:19], 0, v68
	v_add_u32_e32 v68, 1, v64
	s_nop 0
	v_cndmask_b32_e64 v66, v64, v66, s[18:19]
	v_fma_f32 v64, -v68, v64, v32
	v_cmp_lt_f32_e64 s[18:19], 0, v64
	s_nop 1
	v_cndmask_b32_e64 v64, v66, v68, s[18:19]
	v_mul_f32_e32 v66, 0x37800000, v64
	v_cndmask_b32_e32 v64, v64, v66, vcc
	v_cmp_class_f32_e32 vcc, v32, v75
	s_nop 1
	v_cndmask_b32_e32 v32, v64, v32, vcc
	v_div_scale_f32 v64, s[0:1], v32, v32, 1.0
	v_rcp_f32_e32 v66, v64
	s_nop 0
	v_fma_f32 v68, -v64, v66, 1.0
	v_fmac_f32_e32 v66, v68, v66
	v_div_scale_f32 v68, vcc, 1.0, v32, 1.0
	v_mul_f32_e32 v69, v68, v66
	v_fma_f32 v79, -v64, v69, v68
	v_fmac_f32_e32 v69, v79, v66
	v_fma_f32 v64, -v64, v69, v68
	v_div_fmas_f32 v64, v64, v66, v69
	v_div_fixup_f32 v68, v64, v32, 1.0
	v_fmamk_f32 v32, v33, 0x3b800000, v74
	v_cmp_gt_f32_e32 vcc, s6, v32
	v_mul_f32_e32 v33, 0x4f800000, v32
	s_nop 0
	v_cndmask_b32_e32 v32, v32, v33, vcc
	v_sqrt_f32_e32 v33, v32
	s_nop 0
	v_add_u32_e32 v64, -1, v33
	v_fma_f32 v66, -v64, v33, v32
	v_cmp_ge_f32_e64 s[18:19], 0, v66
	v_add_u32_e32 v66, 1, v33
	s_nop 0
	v_cndmask_b32_e64 v64, v33, v64, s[18:19]
	v_fma_f32 v33, -v66, v33, v32
	v_cmp_lt_f32_e64 s[18:19], 0, v33
	s_nop 1
	v_cndmask_b32_e64 v33, v64, v66, s[18:19]
	v_mul_f32_e32 v64, 0x37800000, v33
	v_cndmask_b32_e32 v33, v33, v64, vcc
	v_cmp_class_f32_e32 vcc, v32, v75
	s_nop 1
	v_cndmask_b32_e32 v32, v33, v32, vcc
	v_div_scale_f32 v33, s[0:1], v32, v32, 1.0
	v_rcp_f32_e32 v64, v33
	s_nop 0
	v_fma_f32 v66, -v33, v64, 1.0
	v_fmac_f32_e32 v64, v66, v64
	v_div_scale_f32 v66, vcc, 1.0, v32, 1.0
	v_mul_f32_e32 v69, v66, v64
	v_fma_f32 v79, -v33, v69, v66
	v_fmac_f32_e32 v69, v79, v64
	v_fma_f32 v33, -v33, v69, v66
	v_pk_mul_f32 v[82:83], v[82:83], v[68:69] op_sel_hi:[1,0]
	v_pk_mul_f32 v[70:71], v[80:81], v[68:69] op_sel_hi:[1,0]
	v_div_fmas_f32 v33, v33, v64, v69
	v_pk_mul_f32 v[70:71], v[4:5], v[70:71]
	v_pk_mul_f32 v[80:81], v[2:3], v[82:83]
	v_div_fixup_f32 v32, v33, v32, 1.0
	v_cvt_pk_bf16_f32 v80, v80, v81
	v_cvt_pk_bf16_f32 v81, v70, v71
	v_mad_i64_i32 v[70:71], s[0:1], s22, v76, v[48:49]
	global_store_dwordx2 v[70:71], v[80:81], off
	s_and_saveexec_b64 s[0:1], s[10:11]
	s_xor_b64 s[18:19], exec, s[0:1]
	s_cbranch_execz .LBB0_2257
	v_mov_b32_e32 v66, v65
	v_pk_mul_f32 v[64:65], v[66:67], v[32:33] op_sel_hi:[1,0]
	v_pk_mul_f32 v[30:31], v[30:31], v[32:33] op_sel_hi:[1,0]
	v_pk_mul_f32 v[32:33], v[8:9], v[64:65]
	v_pk_mul_f32 v[30:31], v[6:7], v[30:31]
	s_lshl_b64 s[0:1], s[22:23], 9
	v_cvt_pk_bf16_f32 v30, v30, v31
	v_cvt_pk_bf16_f32 v31, v32, v33
	v_lshl_add_u64 v[32:33], v[44:45], 0, s[0:1]
	global_store_dwordx2 v[32:33], v[30:31], off
.LBB0_2257:
	s_andn2_saveexec_b64 s[18:19], s[18:19]
	s_cbranch_execz .LBB0_2259
	v_mov_b32_e32 v69, v68
	v_mov_b32_e32 v80, v68
	v_mov_b32_e32 v81, v68
	v_mov_b32_e32 v66, v65
	v_pk_mul_f32 v[64:65], v[66:67], v[80:81]
	v_pk_mul_f32 v[30:31], v[30:31], v[68:69]
	v_pk_mul_f32 v[64:65], v[8:9], v[64:65]
	v_pk_mul_f32 v[30:31], v[6:7], v[30:31]
	s_lshl_b64 s[0:1], s[22:23], 9
	v_cvt_pk_bf16_f32 v30, v30, v31
	v_cvt_pk_bf16_f32 v31, v64, v65
	global_store_dwordx2 v[70:71], v[30:31], off offset:512
	v_pk_mul_f32 v[30:31], v[62:63], v[32:33] op_sel_hi:[1,0]
	v_pk_mul_f32 v[32:33], v[60:61], v[32:33] op_sel_hi:[1,0]
	v_pk_mul_f32 v[30:31], v[12:13], v[30:31]
	v_pk_mul_f32 v[32:33], v[10:11], v[32:33]
	s_nop 0
	v_cvt_pk_bf16_f32 v32, v32, v33
	v_cvt_pk_bf16_f32 v33, v30, v31
	v_lshl_add_u64 v[30:31], v[50:51], 0, s[0:1]
	global_store_dwordx2 v[30:31], v[32:33], off offset:256
.LBB0_2259:
	s_or_b64 exec, exec, s[18:19]
	ds_bpermute_b32 v30, v72, v60
	ds_bpermute_b32 v31, v72, v61
	ds_bpermute_b32 v32, v72, v62
	ds_bpermute_b32 v33, v72, v63
	s_and_saveexec_b64 s[18:19], s[14:15]
	s_cbranch_execz .LBB0_2254
	s_waitcnt lgkmcnt(0)
	v_pk_mul_f32 v[26:27], v[26:27], v[30:31]
	v_pk_mul_f32 v[28:29], v[28:29], v[32:33]
	v_xor_b32_e32 v32, 0x80000000, v26
	v_xor_b32_e32 v33, 0x80000000, v27
	v_cndmask_b32_e64 v27, v33, v27, s[16:17]
	v_cndmask_b32_e64 v26, v32, v26, s[16:17]
	v_pk_fma_f32 v[22:23], v[22:23], v[60:61], v[26:27]
	v_mov_b32_e32 v26, 0
	v_med3_f32 v22, v22, s7, v77
	v_med3_f32 v23, v23, s7, v77
	s_ashr_i32 s24, s22, 8
	v_xor_b32_e32 v30, 0x80000000, v28
	v_xor_b32_e32 v31, 0x80000000, v29
	v_cvt_pk_fp8_f32 v26, v22, v23
	s_and_b32 s0, s24, -8
	v_cndmask_b32_e64 v29, v31, v29, s[16:17]
	v_cndmask_b32_e64 v28, v30, v28, s[16:17]
	s_ashr_i32 s1, s0, 31
	v_pk_fma_f32 v[24:25], v[24:25], v[62:63], v[28:29]
	s_and_b32 s21, s22, 0x7ff
	s_lshl_b64 s[22:23], s[0:1], 11
	v_med3_f32 v22, v24, s7, v77
	v_med3_f32 v23, v25, s7, v77
	s_or_b32 s1, s22, s21
	v_cvt_pk_fp8_f32 v26, v22, v23 op_sel:[0,0,1]
	s_mul_i32 s25, s23, 0xc0
	v_mad_u64_u32 v[22:23], s[22:23], s1, v78, v[52:53]
	s_or_b32 s22, s0, 1
	s_ashr_i32 s23, s22, 31
	s_lshl_b64 s[22:23], s[22:23], 11
	v_add_u32_e32 v23, s25, v23
	s_or_b32 s1, s22, s21
	global_store_dword v[22:23], v26, off offset:128
	s_mul_i32 s25, s23, 0xc0
	v_mad_u64_u32 v[22:23], s[22:23], s1, v78, v[52:53]
	s_or_b32 s22, s0, 2
	s_ashr_i32 s23, s22, 31
	s_lshl_b64 s[22:23], s[22:23], 11
	v_add_u32_e32 v23, s25, v23
	s_or_b32 s1, s22, s21
	global_store_dword v[22:23], v26, off offset:128
	s_mul_i32 s25, s23, 0xc0
	v_mad_u64_u32 v[22:23], s[22:23], s1, v78, v[52:53]
	s_or_b32 s22, s0, 3
	s_ashr_i32 s23, s22, 31
	s_lshl_b64 s[22:23], s[22:23], 11
	v_add_u32_e32 v23, s25, v23
	s_or_b32 s1, s22, s21
	global_store_dword v[22:23], v26, off offset:128
	s_mul_i32 s25, s23, 0xc0
	v_mad_u64_u32 v[22:23], s[22:23], s1, v78, v[52:53]
	s_or_b32 s22, s0, 4
	s_ashr_i32 s23, s22, 31
	s_lshl_b64 s[22:23], s[22:23], 11
	v_add_u32_e32 v23, s25, v23
	s_or_b32 s1, s22, s21
	global_store_dword v[22:23], v26, off offset:128
	s_mul_i32 s25, s23, 0xc0
	v_mad_u64_u32 v[22:23], s[22:23], s1, v78, v[52:53]
	s_or_b32 s22, s0, 5
	s_ashr_i32 s23, s22, 31
	s_lshl_b64 s[22:23], s[22:23], 11
	v_add_u32_e32 v23, s25, v23
	s_or_b32 s1, s22, s21
	s_or_b32 s0, s0, 6
	global_store_dword v[22:23], v26, off offset:128
	s_mul_i32 s25, s23, 0xc0
	v_mad_u64_u32 v[22:23], s[22:23], s1, v78, v[52:53]
	s_ashr_i32 s1, s0, 31
	s_lshl_b64 s[0:1], s[0:1], 11
	v_add_u32_e32 v23, s25, v23
	s_or_b32 s0, s0, s21
	global_store_dword v[22:23], v26, off offset:128
	s_mul_i32 s22, s1, 0xc0
	v_mad_u64_u32 v[22:23], s[0:1], s0, v78, v[52:53]
	s_or_b32 s0, s24, 7
	s_ashr_i32 s1, s0, 31
	s_lshl_b64 s[0:1], s[0:1], 11
	v_add_u32_e32 v23, s22, v23
	s_or_b32 s0, s0, s21
	global_store_dword v[22:23], v26, off offset:128
	s_mul_i32 s21, s1, 0xc0
	v_mad_u64_u32 v[22:23], s[0:1], s0, v78, v[52:53]
	v_add_u32_e32 v23, s21, v23
	global_store_dword v[22:23], v26, off offset:128
	s_branch .LBB0_2254

.LBB0_2325:
	ds_read_b128 v[130:133], v165
	ds_read_b128 v[134:137], v165 offset:1024
	ds_read_b128 v[154:157], v165 offset:2048
	ds_read_b128 v[158:161], v165 offset:3072
	s_add_u32 s36, s34, 0x100
	s_addc_u32 s37, s35, 0
	s_cmp_eq_u32 s59, 2
	s_cselect_b32 s41, s13, s37
	s_cselect_b32 s40, s12, s36
	s_cselect_b32 s39, s15, s58
	s_cselect_b32 s38, s14, s20
	v_lshl_add_u64 v[202:203], s[34:35], 0, v[148:149]
	s_add_i32 m0, s17, 0xc000
	ds_read_b128 v[170:173], v166
	ds_read_b128 v[174:177], v166 offset:1024
	ds_read_b128 v[178:181], v166 offset:2048
	ds_read_b128 v[182:185], v166 offset:3072
	ds_read_b128 v[186:189], v166 offset:4096
	ds_read_b128 v[190:193], v166 offset:5120
	ds_read_b128 v[194:197], v166 offset:6144
	ds_read_b128 v[198:201], v166 offset:7168
	global_load_lds_dwordx4 v[202:203], off
	v_lshl_add_u64 v[202:203], s[34:35], 0, v[146:147]
	s_add_i32 m0, s17, 0xe000
	s_nop 0
	global_load_lds_dwordx4 v[202:203], off
	s_waitcnt lgkmcnt(8)
	s_waitcnt vmcnt(10)
	s_barrier
	s_waitcnt lgkmcnt(0)
	s_waitcnt lgkmcnt(0)
	v_mfma_f32_16x16x32_bf16 v[126:129], v[130:133], v[170:173], v[126:129]
	v_mfma_f32_16x16x32_bf16 v[122:125], v[154:157], v[170:173], v[122:125]
	v_mfma_f32_16x16x32_bf16 v[114:117], v[130:133], v[178:181], v[114:117]
	v_mfma_f32_16x16x32_bf16 v[106:109], v[154:157], v[178:181], v[106:109]
	v_mfma_f32_16x16x32_bf16 v[98:101], v[130:133], v[186:189], v[98:101]
	v_mfma_f32_16x16x32_bf16 v[90:93], v[154:157], v[186:189], v[90:93]
	v_mfma_f32_16x16x32_bf16 v[82:85], v[130:133], v[194:197], v[82:85]
	v_mfma_f32_16x16x32_bf16 v[74:77], v[154:157], v[194:197], v[74:77]
	v_mfma_f32_16x16x32_bf16 v[126:129], v[134:137], v[174:177], v[126:129]
	v_mfma_f32_16x16x32_bf16 v[122:125], v[158:161], v[174:177], v[122:125]
	v_mfma_f32_16x16x32_bf16 v[114:117], v[134:137], v[182:185], v[114:117]
	v_mfma_f32_16x16x32_bf16 v[106:109], v[158:161], v[182:185], v[106:109]
	v_mfma_f32_16x16x32_bf16 v[98:101], v[134:137], v[190:193], v[98:101]
	v_mfma_f32_16x16x32_bf16 v[90:93], v[158:161], v[190:193], v[90:93]
	v_mfma_f32_16x16x32_bf16 v[82:85], v[134:137], v[198:201], v[82:85]
	v_mfma_f32_16x16x32_bf16 v[74:77], v[158:161], v[198:201], v[74:77]
	s_barrier
	s_add_i32 s0, s49, s8
	v_lshl_add_u64 v[218:219], s[38:39], 0, v[142:143]
	s_mov_b32 m0, s0
	ds_read_b128 v[202:205], v167
	ds_read_b128 v[206:209], v167 offset:1024
	ds_read_b128 v[210:213], v167 offset:2048
	ds_read_b128 v[214:217], v167 offset:3072
	global_load_lds_dwordx4 v[218:219], off
	v_lshl_add_u64 v[220:221], s[38:39], 0, v[138:139]
	s_add_i32 m0, s0, 0x2000
	s_nop 0
	global_load_lds_dwordx4 v[220:221], off
	s_waitcnt vmcnt(10)
	s_barrier
	s_waitcnt lgkmcnt(0)
	s_waitcnt lgkmcnt(0)
	v_mfma_f32_16x16x32_bf16 v[118:121], v[202:205], v[170:173], v[118:121]
	v_mfma_f32_16x16x32_bf16 v[110:113], v[210:213], v[170:173], v[110:113]
	v_mfma_f32_16x16x32_bf16 v[102:105], v[202:205], v[178:181], v[102:105]
	v_mfma_f32_16x16x32_bf16 v[94:97], v[210:213], v[178:181], v[94:97]
	v_mfma_f32_16x16x32_bf16 v[86:89], v[202:205], v[186:189], v[86:89]
	v_mfma_f32_16x16x32_bf16 v[78:81], v[210:213], v[186:189], v[78:81]
	v_mfma_f32_16x16x32_bf16 v[70:73], v[202:205], v[194:197], v[70:73]
	v_mfma_f32_16x16x32_bf16 v[66:69], v[210:213], v[194:197], v[66:69]
	v_mfma_f32_16x16x32_bf16 v[118:121], v[206:209], v[174:177], v[118:121]
	v_mfma_f32_16x16x32_bf16 v[110:113], v[214:217], v[174:177], v[110:113]
	v_mfma_f32_16x16x32_bf16 v[102:105], v[206:209], v[182:185], v[102:105]
	v_mfma_f32_16x16x32_bf16 v[94:97], v[214:217], v[182:185], v[94:97]
	v_mfma_f32_16x16x32_bf16 v[86:89], v[206:209], v[190:193], v[86:89]
	v_mfma_f32_16x16x32_bf16 v[78:81], v[214:217], v[190:193], v[78:81]
	v_mfma_f32_16x16x32_bf16 v[70:73], v[206:209], v[198:201], v[70:73]
	v_mfma_f32_16x16x32_bf16 v[66:69], v[214:217], v[198:201], v[66:69]
	s_mov_b32 m0, s17
	v_lshl_add_u64 v[222:223], s[40:41], 0, v[144:145]
	s_barrier
	ds_read_b128 v[170:173], v166 offset:16384
	ds_read_b128 v[174:177], v166 offset:17408
	ds_read_b128 v[178:181], v166 offset:18432
	ds_read_b128 v[182:185], v166 offset:19456
	ds_read_b128 v[186:189], v166 offset:20480
	ds_read_b128 v[190:193], v166 offset:21504
	ds_read_b128 v[194:197], v166 offset:22528
	ds_read_b128 v[198:201], v166 offset:23552
	global_load_lds_dwordx4 v[222:223], off
	v_lshl_add_u64 v[224:225], s[40:41], 0, v[140:141]
	s_mov_b32 m0, s42
	s_nop 0
	global_load_lds_dwordx4 v[224:225], off
	s_waitcnt vmcnt(10)
	s_barrier
	s_waitcnt lgkmcnt(0)
	s_waitcnt lgkmcnt(0)
	v_mfma_f32_16x16x32_bf16 v[62:65], v[130:133], v[170:173], v[62:65]
	v_mfma_f32_16x16x32_bf16 v[58:61], v[154:157], v[170:173], v[58:61]
	v_mfma_f32_16x16x32_bf16 v[50:53], v[130:133], v[178:181], v[50:53]
	v_mfma_f32_16x16x32_bf16 v[42:45], v[154:157], v[178:181], v[42:45]
	v_mfma_f32_16x16x32_bf16 v[34:37], v[130:133], v[186:189], v[34:37]
	v_mfma_f32_16x16x32_bf16 v[26:29], v[154:157], v[186:189], v[26:29]
	v_mfma_f32_16x16x32_bf16 v[18:21], v[130:133], v[194:197], v[18:21]
	v_mfma_f32_16x16x32_bf16 v[10:13], v[154:157], v[194:197], v[10:13]
	v_mfma_f32_16x16x32_bf16 v[62:65], v[134:137], v[174:177], v[62:65]
	v_mfma_f32_16x16x32_bf16 v[58:61], v[158:161], v[174:177], v[58:61]
	v_mfma_f32_16x16x32_bf16 v[50:53], v[134:137], v[182:185], v[50:53]
	v_mfma_f32_16x16x32_bf16 v[42:45], v[158:161], v[182:185], v[42:45]
	v_mfma_f32_16x16x32_bf16 v[34:37], v[134:137], v[190:193], v[34:37]
	v_mfma_f32_16x16x32_bf16 v[26:29], v[158:161], v[190:193], v[26:29]
	v_mfma_f32_16x16x32_bf16 v[18:21], v[134:137], v[198:201], v[18:21]
	v_mfma_f32_16x16x32_bf16 v[10:13], v[158:161], v[198:201], v[10:13]
	s_barrier
	s_add_u32 s0, s38, 0x18000
	s_addc_u32 s1, s39, 0
	s_add_i32 s34, s50, s8
	v_lshl_add_u64 v[130:131], s[0:1], 0, v[142:143]
	s_mov_b32 m0, s34
	s_nop 0
	global_load_lds_dwordx4 v[130:131], off
	v_lshl_add_u64 v[130:131], s[0:1], 0, v[138:139]
	s_add_i32 m0, s34, 0x2000
	s_nop 0
	global_load_lds_dwordx4 v[130:131], off
	s_waitcnt vmcnt(10)
	s_barrier
	v_mfma_f32_16x16x32_bf16 v[54:57], v[202:205], v[170:173], v[54:57]
	v_mfma_f32_16x16x32_bf16 v[46:49], v[210:213], v[170:173], v[46:49]
	v_mfma_f32_16x16x32_bf16 v[38:41], v[202:205], v[178:181], v[38:41]
	v_mfma_f32_16x16x32_bf16 v[30:33], v[210:213], v[178:181], v[30:33]
	v_mfma_f32_16x16x32_bf16 v[22:25], v[202:205], v[186:189], v[22:25]
	v_mfma_f32_16x16x32_bf16 v[14:17], v[210:213], v[186:189], v[14:17]
	v_mfma_f32_16x16x32_bf16 v[6:9], v[202:205], v[194:197], v[6:9]
	v_mfma_f32_16x16x32_bf16 v[2:5], v[210:213], v[194:197], v[2:5]
	v_mfma_f32_16x16x32_bf16 v[54:57], v[206:209], v[174:177], v[54:57]
	v_mfma_f32_16x16x32_bf16 v[46:49], v[214:217], v[174:177], v[46:49]
	v_mfma_f32_16x16x32_bf16 v[38:41], v[206:209], v[182:185], v[38:41]
	v_mfma_f32_16x16x32_bf16 v[30:33], v[214:217], v[182:185], v[30:33]
	v_mfma_f32_16x16x32_bf16 v[22:25], v[206:209], v[190:193], v[22:25]
	v_mfma_f32_16x16x32_bf16 v[14:17], v[214:217], v[190:193], v[14:17]
	v_mfma_f32_16x16x32_bf16 v[6:9], v[206:209], v[198:201], v[6:9]
	v_mfma_f32_16x16x32_bf16 v[2:5], v[214:217], v[198:201], v[2:5]
	s_add_i32 s34, 0, 0x18000
	v_add_u32_e32 v158, s34, v164
	s_barrier
	ds_read_b128 v[130:133], v158
	ds_read_b128 v[134:137], v158 offset:1024
	ds_read_b128 v[154:157], v158 offset:2048
	ds_read_b128 v[158:161], v158 offset:3072
	s_add_u32 s0, s40, 0x18000
	s_addc_u32 s1, s41, 0
	s_mov_b32 m0, s43
	v_lshl_add_u64 v[202:203], s[0:1], 0, v[144:145]
	ds_read_b128 v[170:173], v166 offset:32768
	ds_read_b128 v[174:177], v166 offset:33792
	ds_read_b128 v[178:181], v166 offset:34816
	ds_read_b128 v[182:185], v166 offset:35840
	ds_read_b128 v[186:189], v166 offset:36864
	ds_read_b128 v[190:193], v166 offset:37888
	ds_read_b128 v[194:197], v166 offset:38912
	ds_read_b128 v[198:201], v166 offset:39936
	global_load_lds_dwordx4 v[202:203], off
	v_lshl_add_u64 v[202:203], s[0:1], 0, v[140:141]
	s_mov_b32 m0, s44
	s_nop 0
	global_load_lds_dwordx4 v[202:203], off
	s_waitcnt lgkmcnt(8)
	s_waitcnt vmcnt(10)
	s_barrier
	s_waitcnt lgkmcnt(0)
	s_waitcnt lgkmcnt(0)
	v_mfma_f32_16x16x32_bf16 v[126:129], v[130:133], v[170:173], v[126:129]
	v_mfma_f32_16x16x32_bf16 v[122:125], v[154:157], v[170:173], v[122:125]
	v_mfma_f32_16x16x32_bf16 v[114:117], v[130:133], v[178:181], v[114:117]
	v_mfma_f32_16x16x32_bf16 v[106:109], v[154:157], v[178:181], v[106:109]
	v_mfma_f32_16x16x32_bf16 v[98:101], v[130:133], v[186:189], v[98:101]
	v_mfma_f32_16x16x32_bf16 v[90:93], v[154:157], v[186:189], v[90:93]
	v_mfma_f32_16x16x32_bf16 v[82:85], v[130:133], v[194:197], v[82:85]
	v_mfma_f32_16x16x32_bf16 v[74:77], v[154:157], v[194:197], v[74:77]
	v_mfma_f32_16x16x32_bf16 v[126:129], v[134:137], v[174:177], v[126:129]
	v_mfma_f32_16x16x32_bf16 v[122:125], v[158:161], v[174:177], v[122:125]
	v_mfma_f32_16x16x32_bf16 v[114:117], v[134:137], v[182:185], v[114:117]
	v_mfma_f32_16x16x32_bf16 v[106:109], v[158:161], v[182:185], v[106:109]
	v_mfma_f32_16x16x32_bf16 v[98:101], v[134:137], v[190:193], v[98:101]
	v_mfma_f32_16x16x32_bf16 v[90:93], v[158:161], v[190:193], v[90:93]
	v_mfma_f32_16x16x32_bf16 v[82:85], v[134:137], v[198:201], v[82:85]
	v_mfma_f32_16x16x32_bf16 v[74:77], v[158:161], v[198:201], v[74:77]
	s_barrier
	s_add_i32 s35, 0, 0x1c000
	s_add_i32 s0, s34, s8
	v_add_u32_e32 v169, s35, v164
	v_lshl_add_u64 v[218:219], v[218:219], 0, s[30:31]
	s_mov_b32 m0, s0
	ds_read_b128 v[202:205], v169
	ds_read_b128 v[206:209], v169 offset:1024
	ds_read_b128 v[210:213], v169 offset:2048
	ds_read_b128 v[214:217], v169 offset:3072
	global_load_lds_dwordx4 v[218:219], off
	v_lshl_add_u64 v[218:219], v[220:221], 0, s[30:31]
	s_add_i32 m0, s0, 0x2000
	s_nop 0
	global_load_lds_dwordx4 v[218:219], off
	s_waitcnt vmcnt(10)
	s_barrier
	s_waitcnt lgkmcnt(0)
	s_waitcnt lgkmcnt(0)
	v_mfma_f32_16x16x32_bf16 v[118:121], v[202:205], v[170:173], v[118:121]
	v_mfma_f32_16x16x32_bf16 v[110:113], v[210:213], v[170:173], v[110:113]
	v_mfma_f32_16x16x32_bf16 v[102:105], v[202:205], v[178:181], v[102:105]
	v_mfma_f32_16x16x32_bf16 v[94:97], v[210:213], v[178:181], v[94:97]
	v_mfma_f32_16x16x32_bf16 v[86:89], v[202:205], v[186:189], v[86:89]
	v_mfma_f32_16x16x32_bf16 v[78:81], v[210:213], v[186:189], v[78:81]
	v_mfma_f32_16x16x32_bf16 v[70:73], v[202:205], v[194:197], v[70:73]
	v_mfma_f32_16x16x32_bf16 v[66:69], v[210:213], v[194:197], v[66:69]
	v_mfma_f32_16x16x32_bf16 v[118:121], v[206:209], v[174:177], v[118:121]
	v_mfma_f32_16x16x32_bf16 v[110:113], v[214:217], v[174:177], v[110:113]
	v_mfma_f32_16x16x32_bf16 v[102:105], v[206:209], v[182:185], v[102:105]
	v_mfma_f32_16x16x32_bf16 v[94:97], v[214:217], v[182:185], v[94:97]
	v_mfma_f32_16x16x32_bf16 v[86:89], v[206:209], v[190:193], v[86:89]
	v_mfma_f32_16x16x32_bf16 v[78:81], v[214:217], v[190:193], v[78:81]
	v_mfma_f32_16x16x32_bf16 v[70:73], v[206:209], v[198:201], v[70:73]
	v_mfma_f32_16x16x32_bf16 v[66:69], v[214:217], v[198:201], v[66:69]
	s_mov_b32 m0, s46
	v_lshl_add_u64 v[218:219], v[222:223], 0, s[30:31]
	s_barrier
	ds_read_b128 v[170:173], v166 offset:49152
	ds_read_b128 v[174:177], v166 offset:50176
	ds_read_b128 v[178:181], v166 offset:51200
	ds_read_b128 v[182:185], v166 offset:52224
	ds_read_b128 v[186:189], v166 offset:53248
	ds_read_b128 v[190:193], v166 offset:54272
	ds_read_b128 v[194:197], v166 offset:55296
	ds_read_b128 v[198:201], v166 offset:56320
	global_load_lds_dwordx4 v[218:219], off
	v_lshl_add_u64 v[218:219], v[224:225], 0, s[30:31]
	s_mov_b32 m0, s47
	s_nop 0
	global_load_lds_dwordx4 v[218:219], off
	s_waitcnt vmcnt(10)
	s_barrier
	s_waitcnt lgkmcnt(0)
	s_waitcnt lgkmcnt(0)
	v_mfma_f32_16x16x32_bf16 v[62:65], v[130:133], v[170:173], v[62:65]
	v_mfma_f32_16x16x32_bf16 v[58:61], v[154:157], v[170:173], v[58:61]
	v_mfma_f32_16x16x32_bf16 v[50:53], v[130:133], v[178:181], v[50:53]
	v_mfma_f32_16x16x32_bf16 v[42:45], v[154:157], v[178:181], v[42:45]
	v_mfma_f32_16x16x32_bf16 v[34:37], v[130:133], v[186:189], v[34:37]
	v_mfma_f32_16x16x32_bf16 v[26:29], v[154:157], v[186:189], v[26:29]
	v_mfma_f32_16x16x32_bf16 v[18:21], v[130:133], v[194:197], v[18:21]
	v_mfma_f32_16x16x32_bf16 v[10:13], v[154:157], v[194:197], v[10:13]
	v_mfma_f32_16x16x32_bf16 v[62:65], v[134:137], v[174:177], v[62:65]
	v_mfma_f32_16x16x32_bf16 v[58:61], v[158:161], v[174:177], v[58:61]
	v_mfma_f32_16x16x32_bf16 v[50:53], v[134:137], v[182:185], v[50:53]
	v_mfma_f32_16x16x32_bf16 v[42:45], v[158:161], v[182:185], v[42:45]
	v_mfma_f32_16x16x32_bf16 v[34:37], v[134:137], v[190:193], v[34:37]
	v_mfma_f32_16x16x32_bf16 v[26:29], v[158:161], v[190:193], v[26:29]
	v_mfma_f32_16x16x32_bf16 v[18:21], v[134:137], v[198:201], v[18:21]
	v_mfma_f32_16x16x32_bf16 v[10:13], v[158:161], v[198:201], v[10:13]
	s_barrier
	s_add_u32 s0, s38, 0x18080
	s_addc_u32 s1, s39, 0
	s_add_i32 s34, s35, s8
	v_lshl_add_u64 v[130:131], s[0:1], 0, v[142:143]
	s_mov_b32 m0, s34
	s_nop 0
	global_load_lds_dwordx4 v[130:131], off
	v_lshl_add_u64 v[130:131], s[0:1], 0, v[138:139]
	s_add_i32 m0, s34, 0x2000
	s_nop 0
	global_load_lds_dwordx4 v[130:131], off
	s_waitcnt vmcnt(10)
	s_barrier
	v_mfma_f32_16x16x32_bf16 v[54:57], v[202:205], v[170:173], v[54:57]
	v_mfma_f32_16x16x32_bf16 v[46:49], v[210:213], v[170:173], v[46:49]
	v_mfma_f32_16x16x32_bf16 v[38:41], v[202:205], v[178:181], v[38:41]
	v_mfma_f32_16x16x32_bf16 v[30:33], v[210:213], v[178:181], v[30:33]
	v_mfma_f32_16x16x32_bf16 v[22:25], v[202:205], v[186:189], v[22:25]
	v_mfma_f32_16x16x32_bf16 v[14:17], v[210:213], v[186:189], v[14:17]
	v_mfma_f32_16x16x32_bf16 v[6:9], v[202:205], v[194:197], v[6:9]
	v_mfma_f32_16x16x32_bf16 v[2:5], v[210:213], v[194:197], v[2:5]
	v_mfma_f32_16x16x32_bf16 v[54:57], v[206:209], v[174:177], v[54:57]
	v_mfma_f32_16x16x32_bf16 v[46:49], v[214:217], v[174:177], v[46:49]
	v_mfma_f32_16x16x32_bf16 v[38:41], v[206:209], v[182:185], v[38:41]
	v_mfma_f32_16x16x32_bf16 v[30:33], v[214:217], v[182:185], v[30:33]
	v_mfma_f32_16x16x32_bf16 v[22:25], v[206:209], v[190:193], v[22:25]
	v_mfma_f32_16x16x32_bf16 v[14:17], v[214:217], v[190:193], v[14:17]
	v_mfma_f32_16x16x32_bf16 v[6:9], v[206:209], v[198:201], v[6:9]
	v_mfma_f32_16x16x32_bf16 v[2:5], v[214:217], v[198:201], v[2:5]
	s_add_i32 s59, s59, 2
	s_add_u32 s20, s20, 0x100
	s_addc_u32 s58, s58, 0
	s_cmp_gt_u32 s59, 3
	s_mov_b64 s[34:35], s[36:37]
	s_barrier
	s_cbranch_scc0 .LBB0_2325
	v_mov_b32_e32 v169, v162
	v_mov_b32_e32 v130, v163
	s_mov_b64 s[34:35], -1
	v_lshlrev_b32_e32 v154, 3, v130
	s_cmp_gt_i32 s57, 3
	v_ashrrev_i32_e32 v155, 31, v154
	s_cbranch_scc0 .LBB0_2328
	s_lshl_b32 s0, s56, 8
	s_add_i32 s0, s0, s45
	v_add_u32_e32 v248, s0, v169
	v_mov_b32_e32 v136, v248
	v_lshlrev_b64 v[132:133], 2, v[154:155]
	v_ashrrev_i32_e32 v137, 31, v136
	v_lshl_add_u64 v[130:131], s[26:27], 0, v[132:133]
	v_lshlrev_b64 v[134:135], 7, v[136:137]
	v_lshl_add_u64 v[156:157], v[130:131], 0, v[134:135]
	v_lshl_add_u64 v[132:133], s[24:25], 0, v[132:133]
	global_load_dwordx4 v[170:173], v[156:157], off
	global_load_dwordx4 v[174:177], v[156:157], off offset:16
	v_lshl_add_u64 v[134:135], v[132:133], 0, v[134:135]
	global_load_dwordx4 v[178:181], v[134:135], off
	global_load_dwordx4 v[182:185], v[134:135], off offset:16
	v_add_u32_e32 v160, 16, v136
	v_ashrrev_i32_e32 v161, 31, v160
	v_lshlrev_b64 v[134:135], 7, v[160:161]
	v_lshl_add_u64 v[156:157], v[130:131], 0, v[134:135]
	global_load_dwordx4 v[186:189], v[156:157], off
	global_load_dwordx4 v[194:197], v[156:157], off offset:16
	v_lshl_add_u64 v[134:135], v[132:133], 0, v[134:135]
	global_load_dwordx4 v[190:193], v[134:135], off
	global_load_dwordx4 v[198:201], v[134:135], off offset:16
	v_add_u32_e32 v238, 32, v136
	v_add_u32_e32 v134, 48, v136
	v_ashrrev_i32_e32 v239, 31, v238
	v_ashrrev_i32_e32 v135, 31, v134
	v_lshlrev_b64 v[202:203], 7, v[238:239]
	v_lshlrev_b64 v[204:205], 7, v[134:135]
	v_lshl_add_u64 v[206:207], v[132:133], 0, v[202:203]
	v_lshl_add_u64 v[214:215], v[130:131], 0, v[202:203]
	v_lshl_add_u64 v[222:223], v[132:133], 0, v[204:205]
	v_lshl_add_u64 v[230:231], v[130:131], 0, v[204:205]
	global_load_dwordx4 v[202:205], v[206:207], off
	s_nop 0
	global_load_dwordx4 v[206:209], v[206:207], off offset:16
	s_nop 0
	global_load_dwordx4 v[210:213], v[214:215], off
	s_nop 0
	global_load_dwordx4 v[214:217], v[214:215], off offset:16
	s_nop 0
	global_load_dwordx4 v[218:221], v[222:223], off
	s_nop 0
	global_load_dwordx4 v[222:225], v[222:223], off offset:16
	s_nop 0
	global_load_dwordx4 v[226:229], v[230:231], off
	s_nop 0
	global_load_dwordx4 v[230:233], v[230:231], off offset:16
	v_mov_b32_e32 v234, 0
	v_mov_b32_e32 v235, 0
	v_mov_b32_e32 v236, 0
	v_mov_b32_e32 v237, 0
	s_lshl_b32 s0, s57, 2
	s_add_i32 s0, s48, s0
	v_mov_b64_e32 v[156:157], s[22:23]
	s_mul_i32 s20, s0, 0xc0
	v_lshl_add_u64 v[158:159], s[20:21], 0, v[154:155]
	v_mad_i64_i32 v[136:137], s[0:1], v136, s52, v[156:157]
	v_lshl_add_u64 v[136:137], v[136:137], 0, v[158:159]
	s_mov_b64 s[34:35], 0
	s_waitcnt vmcnt(0) lgkmcnt(0)
	v_pk_mul_f32 v[240:241], v[120:121], v[172:173]
	v_pk_mul_f32 v[242:243], v[118:119], v[170:171]
	v_pk_mul_f32 v[172:173], v[128:129], v[172:173]
	v_pk_mul_f32 v[246:247], v[110:111], v[174:175]
	v_pk_mul_f32 v[170:171], v[126:127], v[170:171]
	v_pk_mul_f32 v[174:175], v[122:123], v[174:175]
	v_pk_fma_f32 v[240:241], v[128:129], v[180:181], v[240:241] neg_lo:[0,0,1] neg_hi:[0,0,1]
	v_pk_fma_f32 v[242:243], v[126:127], v[178:179], v[242:243] neg_lo:[0,0,1] neg_hi:[0,0,1]
	v_pk_fma_f32 v[172:173], v[120:121], v[180:181], v[172:173]
	v_pk_fma_f32 v[180:181], v[122:123], v[182:183], v[246:247] neg_lo:[0,0,1] neg_hi:[0,0,1]
	v_pk_fma_f32 v[170:171], v[118:119], v[178:179], v[170:171]
	v_pk_fma_f32 v[174:175], v[110:111], v[182:183], v[174:175]
	v_med3_f32 v135, v242, s51, v168
	v_med3_f32 v161, v243, s51, v168
	v_med3_f32 v180, v180, s51, v168
	v_med3_f32 v181, v181, s51, v168
	v_med3_f32 v170, v170, s51, v168
	v_med3_f32 v171, v171, s51, v168
	v_med3_f32 v174, v174, s51, v168
	v_med3_f32 v175, v175, s51, v168
	v_cvt_pk_fp8_f32 v234, v135, v161
	v_cvt_pk_fp8_f32 v235, v180, v181
	v_pk_mul_f32 v[244:245], v[112:113], v[176:177]
	v_cvt_pk_fp8_f32 v236, v170, v171
	v_cvt_pk_fp8_f32 v237, v174, v175
	v_pk_mul_f32 v[176:177], v[124:125], v[176:177]
	v_pk_fma_f32 v[178:179], v[124:125], v[184:185], v[244:245] neg_lo:[0,0,1] neg_hi:[0,0,1]
	v_pk_fma_f32 v[176:177], v[112:113], v[184:185], v[176:177]
	v_med3_f32 v184, v240, s51, v168
	v_med3_f32 v185, v241, s51, v168
	v_med3_f32 v178, v178, s51, v168
	v_med3_f32 v179, v179, s51, v168
	v_med3_f32 v172, v172, s51, v168
	v_med3_f32 v173, v173, s51, v168
	v_med3_f32 v176, v176, s51, v168
	v_med3_f32 v177, v177, s51, v168
	v_cvt_pk_fp8_f32 v234, v184, v185 op_sel:[0,0,1]
	v_cvt_pk_fp8_f32 v235, v178, v179 op_sel:[0,0,1]
	v_cvt_pk_fp8_f32 v236, v172, v173 op_sel:[0,0,1]
	v_cvt_pk_fp8_f32 v237, v176, v177 op_sel:[0,0,1]
	v_pk_mul_f32 v[170:171], v[102:103], v[186:187]
	v_pk_mul_f32 v[182:183], v[104:105], v[188:189]
	global_store_dwordx2 v[136:137], v[234:235], off offset:128
	global_store_dwordx2 v[136:137], v[236:237], off offset:160
	v_pk_fma_f32 v[136:137], v[114:115], v[190:191], v[170:171] neg_lo:[0,0,1] neg_hi:[0,0,1]
	v_pk_mul_f32 v[178:179], v[94:95], v[194:195]
	v_pk_fma_f32 v[172:173], v[116:117], v[192:193], v[182:183] neg_lo:[0,0,1] neg_hi:[0,0,1]
	v_pk_fma_f32 v[178:179], v[106:107], v[198:199], v[178:179] neg_lo:[0,0,1] neg_hi:[0,0,1]
	v_med3_f32 v135, v136, s51, v168
	v_med3_f32 v137, v137, s51, v168
	v_mov_b32_e32 v136, 0
	v_cvt_pk_fp8_f32 v136, v135, v137
	v_med3_f32 v135, v172, s51, v168
	v_med3_f32 v161, v173, s51, v168
	v_med3_f32 v172, v178, s51, v168
	v_med3_f32 v173, v179, s51, v168
	v_mov_b32_e32 v137, 0
	v_cvt_pk_fp8_f32 v137, v172, v173
	v_pk_mul_f32 v[176:177], v[96:97], v[196:197]
	v_pk_mul_f32 v[174:175], v[114:115], v[186:187]
	v_pk_fma_f32 v[176:177], v[108:109], v[200:201], v[176:177] neg_lo:[0,0,1] neg_hi:[0,0,1]
	v_pk_mul_f32 v[170:171], v[116:117], v[188:189]
	v_pk_fma_f32 v[174:175], v[102:103], v[190:191], v[174:175]
	v_pk_mul_f32 v[182:183], v[106:107], v[194:195]
	v_cvt_pk_fp8_f32 v136, v135, v161 op_sel:[0,0,1]
	v_med3_f32 v135, v176, s51, v168
	v_med3_f32 v161, v177, s51, v168
	v_pk_fma_f32 v[170:171], v[104:105], v[192:193], v[170:171]
	v_pk_fma_f32 v[182:183], v[94:95], v[198:199], v[182:183]
	v_cvt_pk_fp8_f32 v137, v135, v161 op_sel:[0,0,1]
	v_med3_f32 v135, v174, s51, v168
	v_med3_f32 v161, v175, s51, v168
	v_mov_b32_e32 v172, 0
	v_cvt_pk_fp8_f32 v172, v135, v161
	v_med3_f32 v135, v170, s51, v168
	v_med3_f32 v161, v171, s51, v168
	v_med3_f32 v170, v182, s51, v168
	v_med3_f32 v171, v183, s51, v168
	v_mov_b32_e32 v173, 0
	v_cvt_pk_fp8_f32 v173, v170, v171
	v_pk_mul_f32 v[180:181], v[108:109], v[196:197]
	v_cvt_pk_fp8_f32 v172, v135, v161 op_sel:[0,0,1]
	v_pk_fma_f32 v[180:181], v[96:97], v[200:201], v[180:181]
	v_pk_mul_f32 v[176:177], v[78:79], v[214:215]
	v_med3_f32 v135, v180, s51, v168
	v_med3_f32 v161, v181, s51, v168
	v_cvt_pk_fp8_f32 v173, v135, v161 op_sel:[0,0,1]
	v_mad_i64_i32 v[160:161], s[0:1], v160, s52, v[156:157]
	v_lshl_add_u64 v[160:161], v[160:161], 0, v[158:159]
	global_store_dwordx2 v[160:161], v[136:137], off offset:128
	global_store_dwordx2 v[160:161], v[172:173], off offset:160
	v_pk_mul_f32 v[160:161], v[86:87], v[210:211]
	v_pk_mul_f32 v[136:137], v[88:89], v[212:213]
	v_pk_fma_f32 v[160:161], v[98:99], v[202:203], v[160:161] neg_lo:[0,0,1] neg_hi:[0,0,1]
	v_pk_fma_f32 v[136:137], v[100:101], v[204:205], v[136:137] neg_lo:[0,0,1] neg_hi:[0,0,1]
	v_pk_fma_f32 v[176:177], v[90:91], v[206:207], v[176:177] neg_lo:[0,0,1] neg_hi:[0,0,1]
	v_med3_f32 v135, v160, s51, v168
	v_med3_f32 v161, v161, s51, v168
	v_mov_b32_e32 v160, 0
	v_cvt_pk_fp8_f32 v160, v135, v161
	v_med3_f32 v135, v136, s51, v168
	v_med3_f32 v136, v137, s51, v168
	v_med3_f32 v137, v176, s51, v168
	v_med3_f32 v176, v177, s51, v168
	v_mov_b32_e32 v161, 0
	v_cvt_pk_fp8_f32 v161, v137, v176
	v_pk_mul_f32 v[174:175], v[80:81], v[216:217]
	v_pk_mul_f32 v[172:173], v[98:99], v[210:211]
	v_pk_fma_f32 v[174:175], v[92:93], v[208:209], v[174:175] neg_lo:[0,0,1] neg_hi:[0,0,1]
	v_pk_mul_f32 v[170:171], v[100:101], v[212:213]
	v_pk_fma_f32 v[172:173], v[86:87], v[202:203], v[172:173]
	v_pk_mul_f32 v[180:181], v[90:91], v[214:215]
	v_cvt_pk_fp8_f32 v160, v135, v136 op_sel:[0,0,1]
	v_med3_f32 v135, v174, s51, v168
	v_med3_f32 v136, v175, s51, v168
	v_pk_fma_f32 v[170:171], v[88:89], v[204:205], v[170:171]
	v_pk_fma_f32 v[180:181], v[78:79], v[206:207], v[180:181]
	v_cvt_pk_fp8_f32 v161, v135, v136 op_sel:[0,0,1]
	v_med3_f32 v135, v172, s51, v168
	v_med3_f32 v137, v173, s51, v168
	v_mov_b32_e32 v136, 0
	v_cvt_pk_fp8_f32 v136, v135, v137
	v_med3_f32 v135, v170, s51, v168
	v_med3_f32 v170, v171, s51, v168
	v_med3_f32 v171, v180, s51, v168
	v_med3_f32 v172, v181, s51, v168
	v_mov_b32_e32 v137, 0
	v_cvt_pk_fp8_f32 v137, v171, v172
	v_pk_mul_f32 v[178:179], v[92:93], v[216:217]
	v_cvt_pk_fp8_f32 v136, v135, v170 op_sel:[0,0,1]
	v_pk_fma_f32 v[178:179], v[80:81], v[208:209], v[178:179]
	v_pk_mul_f32 v[176:177], v[66:67], v[230:231]
	v_med3_f32 v135, v178, s51, v168
	v_med3_f32 v170, v179, s51, v168
	v_cvt_pk_fp8_f32 v137, v135, v170 op_sel:[0,0,1]
	v_mad_i64_i32 v[170:171], s[0:1], v238, s52, v[156:157]
	v_lshl_add_u64 v[170:171], v[170:171], 0, v[158:159]
	global_store_dwordx2 v[170:171], v[160:161], off offset:128
	global_store_dwordx2 v[170:171], v[136:137], off offset:160
	v_pk_mul_f32 v[160:161], v[70:71], v[226:227]
	v_pk_mul_f32 v[136:137], v[72:73], v[228:229]
	v_pk_fma_f32 v[160:161], v[82:83], v[218:219], v[160:161] neg_lo:[0,0,1] neg_hi:[0,0,1]
	v_pk_fma_f32 v[136:137], v[84:85], v[220:221], v[136:137] neg_lo:[0,0,1] neg_hi:[0,0,1]
	v_pk_fma_f32 v[176:177], v[74:75], v[222:223], v[176:177] neg_lo:[0,0,1] neg_hi:[0,0,1]
	v_med3_f32 v135, v160, s51, v168
	v_med3_f32 v161, v161, s51, v168
	v_mov_b32_e32 v160, 0
	v_cvt_pk_fp8_f32 v160, v135, v161
	v_med3_f32 v135, v136, s51, v168
	v_med3_f32 v136, v137, s51, v168
	v_med3_f32 v137, v176, s51, v168
	v_med3_f32 v176, v177, s51, v168
	v_mov_b32_e32 v161, 0
	v_cvt_pk_fp8_f32 v161, v137, v176
	v_pk_mul_f32 v[174:175], v[68:69], v[232:233]
	v_pk_mul_f32 v[172:173], v[82:83], v[226:227]
	v_pk_fma_f32 v[174:175], v[76:77], v[224:225], v[174:175] neg_lo:[0,0,1] neg_hi:[0,0,1]
	v_pk_mul_f32 v[170:171], v[84:85], v[228:229]
	v_pk_fma_f32 v[172:173], v[70:71], v[218:219], v[172:173]
	v_pk_mul_f32 v[180:181], v[74:75], v[230:231]
	v_cvt_pk_fp8_f32 v160, v135, v136 op_sel:[0,0,1]
	v_med3_f32 v135, v174, s51, v168
	v_med3_f32 v136, v175, s51, v168
	v_pk_fma_f32 v[170:171], v[72:73], v[220:221], v[170:171]
	v_pk_fma_f32 v[180:181], v[66:67], v[222:223], v[180:181]
	v_cvt_pk_fp8_f32 v161, v135, v136 op_sel:[0,0,1]
	v_med3_f32 v135, v172, s51, v168
	v_med3_f32 v137, v173, s51, v168
	v_mov_b32_e32 v136, 0
	v_cvt_pk_fp8_f32 v136, v135, v137
	v_med3_f32 v135, v170, s51, v168
	v_med3_f32 v170, v171, s51, v168
	v_med3_f32 v171, v180, s51, v168
	v_med3_f32 v172, v181, s51, v168
	v_mov_b32_e32 v137, 0
	v_cvt_pk_fp8_f32 v137, v171, v172
	v_pk_mul_f32 v[178:179], v[76:77], v[232:233]
	v_cvt_pk_fp8_f32 v136, v135, v170 op_sel:[0,0,1]
	v_pk_fma_f32 v[178:179], v[68:69], v[224:225], v[178:179]
	v_add_u32_e32 v226, 0x80, v248
	v_med3_f32 v135, v178, s51, v168
	v_med3_f32 v170, v179, s51, v168
	v_cvt_pk_fp8_f32 v137, v135, v170 op_sel:[0,0,1]
	v_mad_i64_i32 v[134:135], s[0:1], v134, s52, v[156:157]
	v_lshl_add_u64 v[134:135], v[134:135], 0, v[158:159]
	global_store_dwordx2 v[134:135], v[160:161], off offset:128
	global_store_dwordx2 v[134:135], v[136:137], off offset:160
	s_nop 0
	v_ashrrev_i32_e32 v227, 31, v226
	v_lshlrev_b64 v[134:135], 7, v[226:227]
	v_lshl_add_u64 v[136:137], v[130:131], 0, v[134:135]
	global_load_dwordx4 v[170:173], v[136:137], off
	v_lshl_add_u64 v[134:135], v[132:133], 0, v[134:135]
	global_load_dwordx4 v[174:177], v[134:135], off
	global_load_dwordx4 v[178:181], v[136:137], off offset:16
	global_load_dwordx4 v[182:185], v[134:135], off offset:16
	v_add_u32_e32 v228, 16, v226
	v_ashrrev_i32_e32 v229, 31, v228
	v_lshlrev_b64 v[134:135], 7, v[228:229]
	v_lshl_add_u64 v[136:137], v[130:131], 0, v[134:135]
	global_load_dwordx4 v[186:189], v[136:137], off
	v_lshl_add_u64 v[134:135], v[132:133], 0, v[134:135]
	global_load_dwordx4 v[190:193], v[134:135], off
	global_load_dwordx4 v[194:197], v[136:137], off offset:16
	global_load_dwordx4 v[198:201], v[134:135], off offset:16
	v_add_u32_e32 v230, 32, v226
	v_ashrrev_i32_e32 v231, 31, v230
	v_lshlrev_b64 v[134:135], 7, v[230:231]
	v_lshl_add_u64 v[136:137], v[132:133], 0, v[134:135]
	v_lshl_add_u64 v[134:135], v[130:131], 0, v[134:135]
	global_load_dwordx4 v[202:205], v[136:137], off
	global_load_dwordx4 v[206:209], v[136:137], off offset:16
	global_load_dwordx4 v[210:213], v[134:135], off
	global_load_dwordx4 v[214:217], v[134:135], off offset:16
	v_add_u32_e32 v160, 48, v226
	v_ashrrev_i32_e32 v161, 31, v160
	v_lshlrev_b64 v[134:135], 7, v[160:161]
	v_lshl_add_u64 v[132:133], v[132:133], 0, v[134:135]
	v_lshl_add_u64 v[134:135], v[130:131], 0, v[134:135]
	global_load_dwordx4 v[218:221], v[132:133], off
	s_nop 0
	global_load_dwordx4 v[130:133], v[132:133], off offset:16
	s_nop 0
	global_load_dwordx4 v[222:225], v[134:135], off
	s_nop 0
	global_load_dwordx4 v[134:137], v[134:135], off offset:16
	s_waitcnt vmcnt(0) lgkmcnt(0)
	v_pk_mul_f32 v[232:233], v[56:57], v[172:173]
	v_pk_mul_f32 v[234:235], v[54:55], v[170:171]
	v_pk_mul_f32 v[172:173], v[64:65], v[172:173]
	v_pk_fma_f32 v[232:233], v[64:65], v[176:177], v[232:233] neg_lo:[0,0,1] neg_hi:[0,0,1]
	v_pk_fma_f32 v[234:235], v[62:63], v[174:175], v[234:235] neg_lo:[0,0,1] neg_hi:[0,0,1]
	v_pk_fma_f32 v[172:173], v[56:57], v[176:177], v[172:173]
	v_pk_mul_f32 v[176:177], v[46:47], v[178:179]
	v_pk_mul_f32 v[178:179], v[58:59], v[178:179]
	v_pk_fma_f32 v[176:177], v[58:59], v[182:183], v[176:177] neg_lo:[0,0,1] neg_hi:[0,0,1]
	v_pk_fma_f32 v[178:179], v[46:47], v[182:183], v[178:179]
	v_med3_f32 v161, v234, s51, v168
	v_med3_f32 v183, v235, s51, v168
	v_mov_b32_e32 v182, 0
	v_cvt_pk_fp8_f32 v182, v161, v183
	v_med3_f32 v176, v176, s51, v168
	v_med3_f32 v177, v177, s51, v168
	v_mov_b32_e32 v183, 0
	v_pk_mul_f32 v[170:171], v[62:63], v[170:171]
	v_cvt_pk_fp8_f32 v183, v176, v177
	v_pk_fma_f32 v[170:171], v[54:55], v[174:175], v[170:171]
	v_pk_mul_f32 v[174:175], v[48:49], v[180:181]
	v_pk_mul_f32 v[180:181], v[60:61], v[180:181]
	v_pk_fma_f32 v[174:175], v[60:61], v[184:185], v[174:175] neg_lo:[0,0,1] neg_hi:[0,0,1]
	v_pk_fma_f32 v[180:181], v[48:49], v[184:185], v[180:181]
	v_med3_f32 v161, v232, s51, v168
	v_med3_f32 v184, v233, s51, v168
	v_cvt_pk_fp8_f32 v182, v161, v184 op_sel:[0,0,1]
	v_med3_f32 v161, v174, s51, v168
	v_med3_f32 v174, v175, s51, v168
	v_cvt_pk_fp8_f32 v183, v161, v174 op_sel:[0,0,1]
	v_med3_f32 v161, v170, s51, v168
	v_med3_f32 v171, v171, s51, v168
	v_mov_b32_e32 v170, 0
	v_cvt_pk_fp8_f32 v170, v161, v171
	v_med3_f32 v161, v172, s51, v168
	v_med3_f32 v172, v173, s51, v168
	v_med3_f32 v173, v178, s51, v168
	v_med3_f32 v174, v179, s51, v168
	v_mov_b32_e32 v171, 0
	v_cvt_pk_fp8_f32 v171, v173, v174
	v_cvt_pk_fp8_f32 v170, v161, v172 op_sel:[0,0,1]
	v_med3_f32 v161, v180, s51, v168
	v_med3_f32 v172, v181, s51, v168
	v_cvt_pk_fp8_f32 v171, v161, v172 op_sel:[0,0,1]
	v_mad_i64_i32 v[172:173], s[0:1], v226, s52, v[156:157]
	v_lshl_add_u64 v[172:173], v[172:173], 0, v[158:159]
	global_store_dwordx2 v[172:173], v[182:183], off offset:128
	global_store_dwordx2 v[172:173], v[170:171], off offset:160
	v_pk_mul_f32 v[172:173], v[38:39], v[186:187]
	v_pk_mul_f32 v[170:171], v[40:41], v[188:189]
	v_pk_fma_f32 v[172:173], v[50:51], v[190:191], v[172:173] neg_lo:[0,0,1] neg_hi:[0,0,1]
	v_pk_mul_f32 v[180:181], v[30:31], v[194:195]
	v_pk_fma_f32 v[170:171], v[52:53], v[192:193], v[170:171] neg_lo:[0,0,1] neg_hi:[0,0,1]
	v_pk_fma_f32 v[180:181], v[42:43], v[198:199], v[180:181] neg_lo:[0,0,1] neg_hi:[0,0,1]
	v_med3_f32 v161, v172, s51, v168
	v_med3_f32 v173, v173, s51, v168
	v_mov_b32_e32 v172, 0
	v_cvt_pk_fp8_f32 v172, v161, v173
	v_med3_f32 v161, v170, s51, v168
	v_med3_f32 v170, v171, s51, v168
	v_med3_f32 v171, v180, s51, v168
	v_med3_f32 v180, v181, s51, v168
	v_mov_b32_e32 v173, 0
	v_cvt_pk_fp8_f32 v173, v171, v180
	v_pk_mul_f32 v[178:179], v[32:33], v[196:197]
	v_pk_mul_f32 v[176:177], v[50:51], v[186:187]
	v_pk_fma_f32 v[178:179], v[44:45], v[200:201], v[178:179] neg_lo:[0,0,1] neg_hi:[0,0,1]
	v_pk_mul_f32 v[174:175], v[52:53], v[188:189]
	v_pk_fma_f32 v[176:177], v[38:39], v[190:191], v[176:177]
	v_pk_mul_f32 v[184:185], v[42:43], v[194:195]
	v_cvt_pk_fp8_f32 v172, v161, v170 op_sel:[0,0,1]
	v_med3_f32 v161, v178, s51, v168
	v_med3_f32 v170, v179, s51, v168
	v_pk_fma_f32 v[174:175], v[40:41], v[192:193], v[174:175]
	v_pk_fma_f32 v[184:185], v[30:31], v[198:199], v[184:185]
	v_cvt_pk_fp8_f32 v173, v161, v170 op_sel:[0,0,1]
	v_med3_f32 v161, v176, s51, v168
	v_med3_f32 v171, v177, s51, v168
	v_mov_b32_e32 v170, 0
	v_cvt_pk_fp8_f32 v170, v161, v171
	v_med3_f32 v161, v174, s51, v168
	v_med3_f32 v174, v175, s51, v168
	v_med3_f32 v175, v184, s51, v168
	v_med3_f32 v176, v185, s51, v168
	v_mov_b32_e32 v171, 0
	v_cvt_pk_fp8_f32 v171, v175, v176
	v_pk_mul_f32 v[182:183], v[44:45], v[196:197]
	v_cvt_pk_fp8_f32 v170, v161, v174 op_sel:[0,0,1]
	v_pk_fma_f32 v[182:183], v[32:33], v[200:201], v[182:183]
	v_pk_mul_f32 v[180:181], v[14:15], v[214:215]
	v_med3_f32 v161, v182, s51, v168
	v_med3_f32 v174, v183, s51, v168
	v_cvt_pk_fp8_f32 v171, v161, v174 op_sel:[0,0,1]
	v_mad_i64_i32 v[174:175], s[0:1], v228, s52, v[156:157]
	v_lshl_add_u64 v[174:175], v[174:175], 0, v[158:159]
	global_store_dwordx2 v[174:175], v[172:173], off offset:128
	global_store_dwordx2 v[174:175], v[170:171], off offset:160
	v_pk_mul_f32 v[172:173], v[22:23], v[210:211]
	v_pk_mul_f32 v[170:171], v[24:25], v[212:213]
	v_pk_fma_f32 v[172:173], v[34:35], v[202:203], v[172:173] neg_lo:[0,0,1] neg_hi:[0,0,1]
	v_pk_fma_f32 v[170:171], v[36:37], v[204:205], v[170:171] neg_lo:[0,0,1] neg_hi:[0,0,1]
	v_pk_fma_f32 v[180:181], v[26:27], v[206:207], v[180:181] neg_lo:[0,0,1] neg_hi:[0,0,1]
	v_med3_f32 v161, v172, s51, v168
	v_med3_f32 v173, v173, s51, v168
	v_mov_b32_e32 v172, 0
	v_cvt_pk_fp8_f32 v172, v161, v173
	v_med3_f32 v161, v170, s51, v168
	v_med3_f32 v170, v171, s51, v168
	v_med3_f32 v171, v180, s51, v168
	v_med3_f32 v180, v181, s51, v168
	v_mov_b32_e32 v173, 0
	v_cvt_pk_fp8_f32 v173, v171, v180
	v_pk_mul_f32 v[178:179], v[16:17], v[216:217]
	v_pk_mul_f32 v[176:177], v[34:35], v[210:211]
	v_pk_fma_f32 v[178:179], v[28:29], v[208:209], v[178:179] neg_lo:[0,0,1] neg_hi:[0,0,1]
	v_pk_mul_f32 v[174:175], v[36:37], v[212:213]
	v_pk_fma_f32 v[176:177], v[22:23], v[202:203], v[176:177]
	v_pk_mul_f32 v[184:185], v[26:27], v[214:215]
	v_cvt_pk_fp8_f32 v172, v161, v170 op_sel:[0,0,1]
	v_med3_f32 v161, v178, s51, v168
	v_med3_f32 v170, v179, s51, v168
	v_pk_fma_f32 v[174:175], v[24:25], v[204:205], v[174:175]
	v_pk_fma_f32 v[184:185], v[14:15], v[206:207], v[184:185]
	v_cvt_pk_fp8_f32 v173, v161, v170 op_sel:[0,0,1]
	v_med3_f32 v161, v176, s51, v168
	v_med3_f32 v171, v177, s51, v168
	v_mov_b32_e32 v170, 0
	v_cvt_pk_fp8_f32 v170, v161, v171
	v_med3_f32 v161, v174, s51, v168
	v_med3_f32 v174, v175, s51, v168
	v_med3_f32 v175, v184, s51, v168
	v_med3_f32 v176, v185, s51, v168
	v_mov_b32_e32 v171, 0
	v_cvt_pk_fp8_f32 v171, v175, v176
	v_pk_mul_f32 v[182:183], v[28:29], v[216:217]
	v_cvt_pk_fp8_f32 v170, v161, v174 op_sel:[0,0,1]
	v_pk_fma_f32 v[182:183], v[16:17], v[208:209], v[182:183]
	v_pk_mul_f32 v[178:179], v[4:5], v[136:137]
	v_med3_f32 v161, v182, s51, v168
	v_med3_f32 v174, v183, s51, v168
	v_cvt_pk_fp8_f32 v171, v161, v174 op_sel:[0,0,1]
	v_mad_i64_i32 v[174:175], s[0:1], v230, s52, v[156:157]
	v_lshl_add_u64 v[174:175], v[174:175], 0, v[158:159]
	global_store_dwordx2 v[174:175], v[172:173], off offset:128
	global_store_dwordx2 v[174:175], v[170:171], off offset:160
	v_pk_mul_f32 v[172:173], v[6:7], v[222:223]
	v_pk_mul_f32 v[170:171], v[8:9], v[224:225]
	v_pk_fma_f32 v[172:173], v[18:19], v[218:219], v[172:173] neg_lo:[0,0,1] neg_hi:[0,0,1]
	v_pk_mul_f32 v[180:181], v[2:3], v[134:135]
	v_pk_mul_f32 v[136:137], v[12:13], v[136:137]
	v_pk_mul_f32 v[134:135], v[10:11], v[134:135]
	v_pk_fma_f32 v[170:171], v[20:21], v[220:221], v[170:171] neg_lo:[0,0,1] neg_hi:[0,0,1]
	v_pk_fma_f32 v[178:179], v[12:13], v[132:133], v[178:179] neg_lo:[0,0,1] neg_hi:[0,0,1]
	v_pk_fma_f32 v[180:181], v[10:11], v[130:131], v[180:181] neg_lo:[0,0,1] neg_hi:[0,0,1]
	v_pk_fma_f32 v[132:133], v[4:5], v[132:133], v[136:137]
	v_pk_fma_f32 v[130:131], v[2:3], v[130:131], v[134:135]
	v_med3_f32 v135, v172, s51, v168
	v_med3_f32 v136, v173, s51, v168
	v_mov_b32_e32 v134, 0
	v_cvt_pk_fp8_f32 v134, v135, v136
	v_med3_f32 v136, v170, s51, v168
	v_med3_f32 v161, v180, s51, v168
	v_med3_f32 v170, v181, s51, v168
	v_mov_b32_e32 v135, 0
	v_cvt_pk_fp8_f32 v135, v161, v170
	v_pk_mul_f32 v[176:177], v[18:19], v[222:223]
	v_med3_f32 v137, v171, s51, v168
	v_pk_fma_f32 v[176:177], v[6:7], v[218:219], v[176:177]
	v_cvt_pk_fp8_f32 v134, v136, v137 op_sel:[0,0,1]
	v_med3_f32 v136, v178, s51, v168
	v_med3_f32 v137, v179, s51, v168
	v_cvt_pk_fp8_f32 v135, v136, v137 op_sel:[0,0,1]
	v_med3_f32 v137, v176, s51, v168
	v_med3_f32 v161, v177, s51, v168
	v_mov_b32_e32 v136, 0
	v_cvt_pk_fp8_f32 v136, v137, v161
	v_med3_f32 v130, v130, s51, v168
	v_med3_f32 v131, v131, s51, v168
	v_mov_b32_e32 v137, 0
	v_cvt_pk_fp8_f32 v137, v130, v131
	v_pk_mul_f32 v[174:175], v[20:21], v[224:225]
	v_med3_f32 v130, v132, s51, v168
	v_pk_fma_f32 v[174:175], v[8:9], v[220:221], v[174:175]
	v_med3_f32 v131, v133, s51, v168
	v_med3_f32 v161, v174, s51, v168
	v_med3_f32 v170, v175, s51, v168
	v_cvt_pk_fp8_f32 v136, v161, v170 op_sel:[0,0,1]
	v_cvt_pk_fp8_f32 v137, v130, v131 op_sel:[0,0,1]
	v_mad_i64_i32 v[130:131], s[0:1], v160, s52, v[156:157]
	v_lshl_add_u64 v[130:131], v[130:131], 0, v[158:159]
	global_store_dwordx2 v[130:131], v[134:135], off offset:128
	global_store_dwordx2 v[130:131], v[136:137], off offset:160
.LBB0_2328:
	s_andn2_b64 vcc, exec, s[34:35]
	s_cbranch_vccnz .LBB0_2317
	v_max_f32_e32 v126, v126, v126
	v_med3_f32 v132, v126, s51, v168
	v_max_f32_e32 v126, v127, v127
	v_med3_f32 v127, v126, s51, v168
	v_mov_b32_e32 v126, 0
	v_cvt_pk_fp8_f32 v126, v132, v127
	v_max_f32_e32 v127, v128, v128
	v_max_f32_e32 v128, v129, v129
	v_med3_f32 v127, v127, s51, v168
	v_med3_f32 v128, v128, s51, v168
	v_max_f32_e32 v118, v118, v118
	v_cvt_pk_fp8_f32 v126, v127, v128 op_sel:[0,0,1]
	v_med3_f32 v128, v118, s51, v168
	v_max_f32_e32 v118, v119, v119
	v_med3_f32 v119, v118, s51, v168
	v_mov_b32_e32 v118, 0
	v_cvt_pk_fp8_f32 v118, v128, v119
	v_max_f32_e32 v122, v122, v122
	v_max_f32_e32 v123, v123, v123
	v_med3_f32 v122, v122, s51, v168
	v_med3_f32 v123, v123, s51, v168
	v_mov_b32_e32 v127, 0
	v_max_f32_e32 v119, v120, v120
	v_max_f32_e32 v120, v121, v121
	v_cvt_pk_fp8_f32 v127, v122, v123
	v_med3_f32 v119, v119, s51, v168
	v_med3_f32 v120, v120, s51, v168
	v_max_f32_e32 v110, v110, v110
	v_max_f32_e32 v111, v111, v111
	s_lshl_b32 s0, s56, 8
	v_cvt_pk_fp8_f32 v118, v119, v120 op_sel:[0,0,1]
	v_med3_f32 v110, v110, s51, v168
	v_med3_f32 v111, v111, s51, v168
	v_mov_b32_e32 v119, 0
	s_add_i32 s0, s0, s45
	v_max_f32_e32 v122, v124, v124
	v_max_f32_e32 v123, v125, v125
	v_cvt_pk_fp8_f32 v119, v110, v111
	v_add_u32_e32 v130, s0, v169
	v_med3_f32 v122, v122, s51, v168
	v_med3_f32 v123, v123, s51, v168
	s_mul_i32 s34, s57, 0x180
	v_mov_b32_e32 v131, v130
	v_cvt_pk_fp8_f32 v127, v122, v123 op_sel:[0,0,1]
	v_mov_b64_e32 v[122:123], s[22:23]
	v_max_f32_e32 v110, v112, v112
	v_max_f32_e32 v111, v113, v113
	s_ashr_i32 s35, s34, 31
	v_med3_f32 v110, v110, s51, v168
	v_mad_i64_i32 v[124:125], s[0:1], v131, s52, v[122:123]
	v_med3_f32 v111, v111, s51, v168
	v_lshl_add_u64 v[124:125], v[124:125], 0, s[34:35]
	v_cvt_pk_fp8_f32 v119, v110, v111 op_sel:[0,0,1]
	v_lshl_add_u64 v[110:111], v[124:125], 0, s[28:29]
	v_lshl_add_u64 v[110:111], v[110:111], 0, v[154:155]
	global_store_dwordx2 v[110:111], v[126:127], off
	global_store_dwordx2 v[110:111], v[118:119], off offset:192
	v_max_f32_e32 v110, v114, v114
	v_med3_f32 v111, v110, s51, v168
	v_max_f32_e32 v110, v115, v115
	v_med3_f32 v113, v110, s51, v168
	v_mov_b32_e32 v110, 0
	v_cvt_pk_fp8_f32 v110, v111, v113
	v_max_f32_e32 v111, v116, v116
	v_max_f32_e32 v113, v117, v117
	v_med3_f32 v111, v111, s51, v168
	v_med3_f32 v113, v113, s51, v168
	v_max_f32_e32 v106, v106, v106
	v_max_f32_e32 v107, v107, v107
	v_cvt_pk_fp8_f32 v110, v111, v113 op_sel:[0,0,1]
	v_med3_f32 v106, v106, s51, v168
	v_med3_f32 v107, v107, s51, v168
	v_mov_b32_e32 v111, 0
	v_max_f32_e32 v102, v102, v102
	v_cvt_pk_fp8_f32 v111, v106, v107
	v_max_f32_e32 v106, v108, v108
	v_med3_f32 v108, v102, s51, v168
	v_max_f32_e32 v102, v103, v103
	v_med3_f32 v103, v102, s51, v168
	v_mov_b32_e32 v102, 0
	v_cvt_pk_fp8_f32 v102, v108, v103
	v_max_f32_e32 v103, v104, v104
	v_max_f32_e32 v104, v105, v105
	v_med3_f32 v103, v103, s51, v168
	v_med3_f32 v104, v104, s51, v168
	v_max_f32_e32 v94, v94, v94
	v_max_f32_e32 v95, v95, v95
	v_cvt_pk_fp8_f32 v102, v103, v104 op_sel:[0,0,1]
	v_med3_f32 v94, v94, s51, v168
	v_med3_f32 v95, v95, s51, v168
	v_mov_b32_e32 v103, 0
	v_cvt_pk_fp8_f32 v103, v94, v95
	v_max_f32_e32 v107, v109, v109
	v_add_u32_e32 v112, 16, v130
	v_med3_f32 v106, v106, s51, v168
	v_med3_f32 v107, v107, s51, v168
	v_max_f32_e32 v94, v96, v96
	v_max_f32_e32 v95, v97, v97
	v_cvt_pk_fp8_f32 v111, v106, v107 op_sel:[0,0,1]
	v_mad_i64_i32 v[106:107], s[0:1], v112, s52, v[122:123]
	v_med3_f32 v94, v94, s51, v168
	v_med3_f32 v95, v95, s51, v168
	v_lshl_add_u64 v[106:107], v[106:107], 0, s[34:35]
	v_cvt_pk_fp8_f32 v103, v94, v95 op_sel:[0,0,1]
	v_lshl_add_u64 v[94:95], v[106:107], 0, s[28:29]
	v_lshl_add_u64 v[94:95], v[94:95], 0, v[154:155]
	global_store_dwordx2 v[94:95], v[110:111], off
	global_store_dwordx2 v[94:95], v[102:103], off offset:192
	v_max_f32_e32 v94, v98, v98
	v_med3_f32 v95, v94, s51, v168
	v_max_f32_e32 v94, v99, v99
	v_med3_f32 v97, v94, s51, v168
	v_mov_b32_e32 v94, 0
	v_cvt_pk_fp8_f32 v94, v95, v97
	v_max_f32_e32 v95, v100, v100
	v_max_f32_e32 v97, v101, v101
	v_med3_f32 v95, v95, s51, v168
	v_med3_f32 v97, v97, s51, v168
	v_max_f32_e32 v90, v90, v90
	v_max_f32_e32 v91, v91, v91
	v_cvt_pk_fp8_f32 v94, v95, v97 op_sel:[0,0,1]
	v_med3_f32 v90, v90, s51, v168
	v_med3_f32 v91, v91, s51, v168
	v_mov_b32_e32 v95, 0
	v_max_f32_e32 v86, v86, v86
	v_cvt_pk_fp8_f32 v95, v90, v91
	v_max_f32_e32 v90, v92, v92
	v_med3_f32 v92, v86, s51, v168
	v_max_f32_e32 v86, v87, v87
	v_med3_f32 v87, v86, s51, v168
	v_mov_b32_e32 v86, 0
	v_cvt_pk_fp8_f32 v86, v92, v87
	v_max_f32_e32 v87, v88, v88
	v_max_f32_e32 v88, v89, v89
	v_med3_f32 v87, v87, s51, v168
	v_med3_f32 v88, v88, s51, v168
	v_max_f32_e32 v78, v78, v78
	v_max_f32_e32 v79, v79, v79
	v_cvt_pk_fp8_f32 v86, v87, v88 op_sel:[0,0,1]
	v_med3_f32 v78, v78, s51, v168
	v_med3_f32 v79, v79, s51, v168
	v_mov_b32_e32 v87, 0
	v_cvt_pk_fp8_f32 v87, v78, v79
	v_max_f32_e32 v91, v93, v93
	v_add_u32_e32 v96, 32, v130
	v_med3_f32 v90, v90, s51, v168
	v_med3_f32 v91, v91, s51, v168
	v_max_f32_e32 v78, v80, v80
	v_max_f32_e32 v79, v81, v81
	v_cvt_pk_fp8_f32 v95, v90, v91 op_sel:[0,0,1]
	v_mad_i64_i32 v[90:91], s[0:1], v96, s52, v[122:123]
	v_med3_f32 v78, v78, s51, v168
	v_med3_f32 v79, v79, s51, v168
	v_lshl_add_u64 v[90:91], v[90:91], 0, s[34:35]
	v_cvt_pk_fp8_f32 v87, v78, v79 op_sel:[0,0,1]
	v_lshl_add_u64 v[78:79], v[90:91], 0, s[28:29]
	v_lshl_add_u64 v[78:79], v[78:79], 0, v[154:155]
	global_store_dwordx2 v[78:79], v[94:95], off
	global_store_dwordx2 v[78:79], v[86:87], off offset:192
	v_max_f32_e32 v78, v82, v82
	v_med3_f32 v79, v78, s51, v168
	v_max_f32_e32 v78, v83, v83
	v_med3_f32 v81, v78, s51, v168
	v_mov_b32_e32 v78, 0
	v_cvt_pk_fp8_f32 v78, v79, v81
	v_max_f32_e32 v79, v84, v84
	v_max_f32_e32 v81, v85, v85
	v_med3_f32 v79, v79, s51, v168
	v_med3_f32 v81, v81, s51, v168
	v_max_f32_e32 v74, v74, v74
	v_max_f32_e32 v75, v75, v75
	v_cvt_pk_fp8_f32 v78, v79, v81 op_sel:[0,0,1]
	v_med3_f32 v74, v74, s51, v168
	v_med3_f32 v75, v75, s51, v168
	v_mov_b32_e32 v79, 0
	v_max_f32_e32 v70, v70, v70
	v_cvt_pk_fp8_f32 v79, v74, v75
	v_max_f32_e32 v74, v76, v76
	v_med3_f32 v76, v70, s51, v168
	v_max_f32_e32 v70, v71, v71
	v_med3_f32 v71, v70, s51, v168
	v_mov_b32_e32 v70, 0
	v_cvt_pk_fp8_f32 v70, v76, v71
	v_max_f32_e32 v71, v72, v72
	v_max_f32_e32 v72, v73, v73
	v_med3_f32 v71, v71, s51, v168
	v_med3_f32 v72, v72, s51, v168
	v_max_f32_e32 v66, v66, v66
	v_max_f32_e32 v67, v67, v67
	v_cvt_pk_fp8_f32 v70, v71, v72 op_sel:[0,0,1]
	v_med3_f32 v66, v66, s51, v168
	v_med3_f32 v67, v67, s51, v168
	v_mov_b32_e32 v71, 0
	v_cvt_pk_fp8_f32 v71, v66, v67
	v_max_f32_e32 v75, v77, v77
	v_add_u32_e32 v80, 48, v130
	v_med3_f32 v74, v74, s51, v168
	v_med3_f32 v75, v75, s51, v168
	v_max_f32_e32 v66, v68, v68
	v_max_f32_e32 v67, v69, v69
	v_cvt_pk_fp8_f32 v79, v74, v75 op_sel:[0,0,1]
	v_mad_i64_i32 v[74:75], s[0:1], v80, s52, v[122:123]
	v_med3_f32 v66, v66, s51, v168
	v_med3_f32 v67, v67, s51, v168
	v_lshl_add_u64 v[74:75], v[74:75], 0, s[34:35]
	v_cvt_pk_fp8_f32 v71, v66, v67 op_sel:[0,0,1]
	v_lshl_add_u64 v[66:67], v[74:75], 0, s[28:29]
	v_lshl_add_u64 v[66:67], v[66:67], 0, v[154:155]
	v_max_f32_e32 v62, v62, v62
	global_store_dwordx2 v[66:67], v[78:79], off
	global_store_dwordx2 v[66:67], v[70:71], off offset:192
	v_med3_f32 v67, v62, s51, v168
	v_max_f32_e32 v62, v63, v63
	v_med3_f32 v63, v62, s51, v168
	v_mov_b32_e32 v62, 0
	v_cvt_pk_fp8_f32 v62, v67, v63
	v_max_f32_e32 v63, v64, v64
	v_max_f32_e32 v64, v65, v65
	v_med3_f32 v63, v63, s51, v168
	v_med3_f32 v64, v64, s51, v168
	v_max_f32_e32 v58, v58, v58
	v_max_f32_e32 v59, v59, v59
	v_cvt_pk_fp8_f32 v62, v63, v64 op_sel:[0,0,1]
	v_med3_f32 v58, v58, s51, v168
	v_med3_f32 v59, v59, s51, v168
	v_mov_b32_e32 v63, 0
	v_max_f32_e32 v54, v54, v54
	v_cvt_pk_fp8_f32 v63, v58, v59
	v_max_f32_e32 v58, v60, v60
	v_med3_f32 v60, v54, s51, v168
	v_max_f32_e32 v54, v55, v55
	v_med3_f32 v55, v54, s51, v168
	v_mov_b32_e32 v54, 0
	v_cvt_pk_fp8_f32 v54, v60, v55
	v_max_f32_e32 v55, v56, v56
	v_max_f32_e32 v56, v57, v57
	v_med3_f32 v55, v55, s51, v168
	v_med3_f32 v56, v56, s51, v168
	v_max_f32_e32 v46, v46, v46
	v_max_f32_e32 v47, v47, v47
	v_cvt_pk_fp8_f32 v54, v55, v56 op_sel:[0,0,1]
	v_med3_f32 v46, v46, s51, v168
	v_med3_f32 v47, v47, s51, v168
	v_mov_b32_e32 v55, 0
	v_cvt_pk_fp8_f32 v55, v46, v47
	v_max_f32_e32 v59, v61, v61
	v_add_u32_e32 v66, 0x80, v130
	v_med3_f32 v58, v58, s51, v168
	v_med3_f32 v59, v59, s51, v168
	v_max_f32_e32 v46, v48, v48
	v_max_f32_e32 v47, v49, v49
	v_cvt_pk_fp8_f32 v63, v58, v59 op_sel:[0,0,1]
	v_mad_i64_i32 v[58:59], s[0:1], v66, s52, v[122:123]
	v_med3_f32 v46, v46, s51, v168
	v_med3_f32 v47, v47, s51, v168
	v_lshl_add_u64 v[58:59], v[58:59], 0, s[34:35]
	v_cvt_pk_fp8_f32 v55, v46, v47 op_sel:[0,0,1]
	v_lshl_add_u64 v[46:47], v[58:59], 0, s[28:29]
	v_lshl_add_u64 v[46:47], v[46:47], 0, v[154:155]
	global_store_dwordx2 v[46:47], v[62:63], off
	global_store_dwordx2 v[46:47], v[54:55], off offset:192
	v_max_f32_e32 v46, v50, v50
	v_med3_f32 v47, v46, s51, v168
	v_max_f32_e32 v46, v51, v51
	v_med3_f32 v49, v46, s51, v168
	v_mov_b32_e32 v46, 0
	v_cvt_pk_fp8_f32 v46, v47, v49
	v_max_f32_e32 v47, v52, v52
	v_max_f32_e32 v49, v53, v53
	v_med3_f32 v47, v47, s51, v168
	v_med3_f32 v49, v49, s51, v168
	v_max_f32_e32 v42, v42, v42
	v_max_f32_e32 v43, v43, v43
	v_cvt_pk_fp8_f32 v46, v47, v49 op_sel:[0,0,1]
	v_med3_f32 v42, v42, s51, v168
	v_med3_f32 v43, v43, s51, v168
	v_mov_b32_e32 v47, 0
	v_max_f32_e32 v38, v38, v38
	v_cvt_pk_fp8_f32 v47, v42, v43
	v_max_f32_e32 v42, v44, v44
	v_med3_f32 v44, v38, s51, v168
	v_max_f32_e32 v38, v39, v39
	v_med3_f32 v39, v38, s51, v168
	v_mov_b32_e32 v38, 0
	v_cvt_pk_fp8_f32 v38, v44, v39
	v_max_f32_e32 v39, v40, v40
	v_max_f32_e32 v40, v41, v41
	v_med3_f32 v39, v39, s51, v168
	v_med3_f32 v40, v40, s51, v168
	v_max_f32_e32 v30, v30, v30
	v_max_f32_e32 v31, v31, v31
	v_cvt_pk_fp8_f32 v38, v39, v40 op_sel:[0,0,1]
	v_med3_f32 v30, v30, s51, v168
	v_med3_f32 v31, v31, s51, v168
	v_mov_b32_e32 v39, 0
	v_cvt_pk_fp8_f32 v39, v30, v31
	v_max_f32_e32 v43, v45, v45
	v_add_u32_e32 v48, 0x90, v130
	v_med3_f32 v42, v42, s51, v168
	v_med3_f32 v43, v43, s51, v168
	v_max_f32_e32 v30, v32, v32
	v_max_f32_e32 v31, v33, v33
	v_cvt_pk_fp8_f32 v47, v42, v43 op_sel:[0,0,1]
	v_mad_i64_i32 v[42:43], s[0:1], v48, s52, v[122:123]
	v_med3_f32 v30, v30, s51, v168
	v_med3_f32 v31, v31, s51, v168
	v_lshl_add_u64 v[42:43], v[42:43], 0, s[34:35]
	v_cvt_pk_fp8_f32 v39, v30, v31 op_sel:[0,0,1]
	v_lshl_add_u64 v[30:31], v[42:43], 0, s[28:29]
	v_lshl_add_u64 v[30:31], v[30:31], 0, v[154:155]
	global_store_dwordx2 v[30:31], v[46:47], off
	global_store_dwordx2 v[30:31], v[38:39], off offset:192
	v_max_f32_e32 v30, v34, v34
	v_med3_f32 v31, v30, s51, v168
	v_max_f32_e32 v30, v35, v35
	v_med3_f32 v33, v30, s51, v168
	v_mov_b32_e32 v30, 0
	v_cvt_pk_fp8_f32 v30, v31, v33
	v_max_f32_e32 v31, v36, v36
	v_max_f32_e32 v33, v37, v37
	v_med3_f32 v31, v31, s51, v168
	v_med3_f32 v33, v33, s51, v168
	v_max_f32_e32 v26, v26, v26
	v_max_f32_e32 v27, v27, v27
	v_cvt_pk_fp8_f32 v30, v31, v33 op_sel:[0,0,1]
	v_med3_f32 v26, v26, s51, v168
	v_med3_f32 v27, v27, s51, v168
	v_mov_b32_e32 v31, 0
	v_max_f32_e32 v22, v22, v22
	v_cvt_pk_fp8_f32 v31, v26, v27
	v_max_f32_e32 v26, v28, v28
	v_med3_f32 v28, v22, s51, v168
	v_max_f32_e32 v22, v23, v23
	v_med3_f32 v23, v22, s51, v168
	v_mov_b32_e32 v22, 0
	v_cvt_pk_fp8_f32 v22, v28, v23
	v_max_f32_e32 v23, v24, v24
	v_max_f32_e32 v24, v25, v25
	v_med3_f32 v23, v23, s51, v168
	v_med3_f32 v24, v24, s51, v168
	v_max_f32_e32 v14, v14, v14
	v_max_f32_e32 v15, v15, v15
	v_cvt_pk_fp8_f32 v22, v23, v24 op_sel:[0,0,1]
	v_med3_f32 v14, v14, s51, v168
	v_med3_f32 v15, v15, s51, v168
	v_mov_b32_e32 v23, 0
	v_cvt_pk_fp8_f32 v23, v14, v15
	v_max_f32_e32 v27, v29, v29
	v_add_u32_e32 v32, 0xa0, v130
	v_med3_f32 v26, v26, s51, v168
	v_med3_f32 v27, v27, s51, v168
	v_max_f32_e32 v14, v16, v16
	v_max_f32_e32 v15, v17, v17
	v_cvt_pk_fp8_f32 v31, v26, v27 op_sel:[0,0,1]
	v_mad_i64_i32 v[26:27], s[0:1], v32, s52, v[122:123]
	v_med3_f32 v14, v14, s51, v168
	v_med3_f32 v15, v15, s51, v168
	v_lshl_add_u64 v[26:27], v[26:27], 0, s[34:35]
	v_cvt_pk_fp8_f32 v23, v14, v15 op_sel:[0,0,1]
	v_lshl_add_u64 v[14:15], v[26:27], 0, s[28:29]
	v_lshl_add_u64 v[14:15], v[14:15], 0, v[154:155]
	global_store_dwordx2 v[14:15], v[30:31], off
	global_store_dwordx2 v[14:15], v[22:23], off offset:192
	v_max_f32_e32 v14, v18, v18
	v_med3_f32 v15, v14, s51, v168
	v_max_f32_e32 v14, v19, v19
	v_med3_f32 v17, v14, s51, v168
	v_mov_b32_e32 v14, 0
	v_cvt_pk_fp8_f32 v14, v15, v17
	v_max_f32_e32 v15, v20, v20
	v_max_f32_e32 v17, v21, v21
	v_med3_f32 v15, v15, s51, v168
	v_med3_f32 v17, v17, s51, v168
	v_max_f32_e32 v10, v10, v10
	v_max_f32_e32 v11, v11, v11
	v_cvt_pk_fp8_f32 v14, v15, v17 op_sel:[0,0,1]
	v_med3_f32 v10, v10, s51, v168
	v_med3_f32 v11, v11, s51, v168
	v_mov_b32_e32 v15, 0
	v_max_f32_e32 v6, v6, v6
	v_cvt_pk_fp8_f32 v15, v10, v11
	v_max_f32_e32 v10, v12, v12
	v_med3_f32 v12, v6, s51, v168
	v_max_f32_e32 v6, v7, v7
	v_med3_f32 v7, v6, s51, v168
	v_mov_b32_e32 v6, 0
	v_cvt_pk_fp8_f32 v6, v12, v7
	v_max_f32_e32 v7, v8, v8
	v_max_f32_e32 v8, v9, v9
	v_med3_f32 v7, v7, s51, v168
	v_med3_f32 v8, v8, s51, v168
	v_max_f32_e32 v2, v2, v2
	v_max_f32_e32 v3, v3, v3
	v_cvt_pk_fp8_f32 v6, v7, v8 op_sel:[0,0,1]
	v_med3_f32 v2, v2, s51, v168
	v_med3_f32 v3, v3, s51, v168
	v_mov_b32_e32 v7, 0
	v_cvt_pk_fp8_f32 v7, v2, v3
	v_max_f32_e32 v11, v13, v13
	v_add_u32_e32 v16, 0xb0, v130
	v_med3_f32 v10, v10, s51, v168
	v_med3_f32 v11, v11, s51, v168
	v_max_f32_e32 v2, v4, v4
	v_max_f32_e32 v3, v5, v5
	v_cvt_pk_fp8_f32 v15, v10, v11 op_sel:[0,0,1]
	v_mad_i64_i32 v[10:11], s[0:1], v16, s52, v[122:123]
	v_med3_f32 v2, v2, s51, v168
	v_med3_f32 v3, v3, s51, v168
	v_lshl_add_u64 v[10:11], v[10:11], 0, s[34:35]
	v_cvt_pk_fp8_f32 v7, v2, v3 op_sel:[0,0,1]
	v_lshl_add_u64 v[2:3], v[10:11], 0, s[28:29]
	v_lshl_add_u64 v[2:3], v[2:3], 0, v[154:155]
	global_store_dwordx2 v[2:3], v[14:15], off
	global_store_dwordx2 v[2:3], v[6:7], off offset:192
	s_branch .LBB0_2317

.LBB0_2344:
	s_add_u32 s39, s30, s38
	s_addc_u32 s40, s31, 0
	s_add_u32 s41, s39, 0x100
	s_addc_u32 s42, s40, 0
	s_and_b64 s[0:1], s[36:37], exec
	s_cselect_b32 s43, s21, s42
	s_cselect_b32 s42, s62, s41
	s_add_u32 s0, s28, s38
	s_addc_u32 s1, s29, 0
	s_add_u32 s38, s0, 0x100
	s_addc_u32 s41, s1, 0
	s_and_b64 s[0:1], s[36:37], exec
	s_cselect_b32 s45, s19, s41
	s_cselect_b32 s44, s63, s38
	s_add_u32 s46, s39, 0x10080
	s_addc_u32 s47, s40, 0
	s_add_i32 s70, s58, s9
	s_add_i32 m0, s27, 0xc000
	s_add_i32 s71, s27, 0xe000
	s_add_i32 s0, s70, 0x2000
	s_add_u32 s40, s44, 0x10000
	s_addc_u32 s41, s45, 0
	s_add_i32 s77, s59, s9
	ds_read_b128 v[152:155], v147
	ds_read_b128 v[156:159], v147 offset:1024
	ds_read_b128 v[160:163], v147 offset:2048
	ds_read_b128 v[164:167], v147 offset:3072
	s_add_i32 s1, s77, 0x2000
	s_add_i32 s73, 0, 0x18000
	s_add_u32 s38, s42, 0x10000
	s_addc_u32 s39, s43, 0
	s_add_i32 s72, s73, s9
	s_add_i32 s69, 0, 0x1c000
	s_add_i32 s67, s72, 0x2000
	s_add_u32 s36, s44, 0x10080
	s_addc_u32 s37, s45, 0
	s_add_i32 s65, s69, s9
	s_add_i32 s64, s65, 0x2000
	v_lshl_add_u64 v[142:143], s[46:47], 0, v[136:137]
	ds_read_b128 v[168:171], v148
	ds_read_b128 v[172:175], v148 offset:1024
	ds_read_b128 v[176:179], v148 offset:2048
	ds_read_b128 v[180:183], v148 offset:3072
	ds_read_b128 v[184:187], v148 offset:4096
	ds_read_b128 v[188:191], v148 offset:5120
	ds_read_b128 v[192:195], v148 offset:6144
	ds_read_b128 v[196:199], v148 offset:7168
	global_load_lds_dwordx4 v[142:143], off
	v_lshl_add_u64 v[142:143], s[46:47], 0, v[132:133]
	s_mov_b32 m0, s71
	s_nop 0
	global_load_lds_dwordx4 v[142:143], off
	s_waitcnt lgkmcnt(8)
	s_waitcnt vmcnt(10)
	s_barrier
	s_waitcnt lgkmcnt(0)
	s_waitcnt lgkmcnt(0)
	v_mfma_f32_16x16x32_bf16 v[126:129], v[152:155], v[168:171], v[126:129]
	v_mfma_f32_16x16x32_bf16 v[122:125], v[160:163], v[168:171], v[122:125]
	v_mfma_f32_16x16x32_bf16 v[110:113], v[152:155], v[176:179], v[110:113]
	v_mfma_f32_16x16x32_bf16 v[106:109], v[160:163], v[176:179], v[106:109]
	v_mfma_f32_16x16x32_bf16 v[94:97], v[152:155], v[184:187], v[94:97]
	v_mfma_f32_16x16x32_bf16 v[90:93], v[160:163], v[184:187], v[90:93]
	v_mfma_f32_16x16x32_bf16 v[78:81], v[152:155], v[192:195], v[78:81]
	v_mfma_f32_16x16x32_bf16 v[74:77], v[160:163], v[192:195], v[74:77]
	v_mfma_f32_16x16x32_bf16 v[126:129], v[156:159], v[172:175], v[126:129]
	v_mfma_f32_16x16x32_bf16 v[122:125], v[164:167], v[172:175], v[122:125]
	v_mfma_f32_16x16x32_bf16 v[110:113], v[156:159], v[180:183], v[110:113]
	v_mfma_f32_16x16x32_bf16 v[106:109], v[164:167], v[180:183], v[106:109]
	v_mfma_f32_16x16x32_bf16 v[94:97], v[156:159], v[188:191], v[94:97]
	v_mfma_f32_16x16x32_bf16 v[90:93], v[164:167], v[188:191], v[90:93]
	v_mfma_f32_16x16x32_bf16 v[78:81], v[156:159], v[196:199], v[78:81]
	v_mfma_f32_16x16x32_bf16 v[74:77], v[164:167], v[196:199], v[74:77]
	s_barrier
	s_mov_b32 m0, s70
	v_lshl_add_u64 v[142:143], s[44:45], 0, v[134:135]
	ds_read_b128 v[200:203], v149
	ds_read_b128 v[204:207], v149 offset:1024
	ds_read_b128 v[208:211], v149 offset:2048
	ds_read_b128 v[212:215], v149 offset:3072
	global_load_lds_dwordx4 v[142:143], off
	v_lshl_add_u64 v[216:217], s[44:45], 0, v[130:131]
	s_mov_b32 m0, s0
	s_nop 0
	global_load_lds_dwordx4 v[216:217], off
	s_waitcnt vmcnt(10)
	s_barrier
	s_waitcnt lgkmcnt(0)
	s_waitcnt lgkmcnt(0)
	v_mfma_f32_16x16x32_bf16 v[118:121], v[200:203], v[168:171], v[118:121]
	v_mfma_f32_16x16x32_bf16 v[114:117], v[208:211], v[168:171], v[114:117]
	v_mfma_f32_16x16x32_bf16 v[102:105], v[200:203], v[176:179], v[102:105]
	v_mfma_f32_16x16x32_bf16 v[98:101], v[208:211], v[176:179], v[98:101]
	v_mfma_f32_16x16x32_bf16 v[86:89], v[200:203], v[184:187], v[86:89]
	v_mfma_f32_16x16x32_bf16 v[82:85], v[208:211], v[184:187], v[82:85]
	v_mfma_f32_16x16x32_bf16 v[70:73], v[200:203], v[192:195], v[70:73]
	v_mfma_f32_16x16x32_bf16 v[66:69], v[208:211], v[192:195], v[66:69]
	v_mfma_f32_16x16x32_bf16 v[118:121], v[204:207], v[172:175], v[118:121]
	v_mfma_f32_16x16x32_bf16 v[114:117], v[212:215], v[172:175], v[114:117]
	v_mfma_f32_16x16x32_bf16 v[102:105], v[204:207], v[180:183], v[102:105]
	v_mfma_f32_16x16x32_bf16 v[98:101], v[212:215], v[180:183], v[98:101]
	v_mfma_f32_16x16x32_bf16 v[86:89], v[204:207], v[188:191], v[86:89]
	v_mfma_f32_16x16x32_bf16 v[82:85], v[212:215], v[188:191], v[82:85]
	v_mfma_f32_16x16x32_bf16 v[70:73], v[204:207], v[196:199], v[70:73]
	v_mfma_f32_16x16x32_bf16 v[66:69], v[212:215], v[196:199], v[66:69]
	s_mov_b32 m0, s27
	v_lshl_add_u64 v[218:219], s[42:43], 0, v[136:137]
	s_barrier
	ds_read_b128 v[168:171], v148 offset:16384
	ds_read_b128 v[172:175], v148 offset:17408
	ds_read_b128 v[176:179], v148 offset:18432
	ds_read_b128 v[180:183], v148 offset:19456
	ds_read_b128 v[184:187], v148 offset:20480
	ds_read_b128 v[188:191], v148 offset:21504
	ds_read_b128 v[192:195], v148 offset:22528
	ds_read_b128 v[196:199], v148 offset:23552
	global_load_lds_dwordx4 v[218:219], off
	v_lshl_add_u64 v[220:221], s[42:43], 0, v[132:133]
	s_mov_b32 m0, s48
	s_nop 0
	global_load_lds_dwordx4 v[220:221], off
	s_waitcnt vmcnt(10)
	s_barrier
	s_waitcnt lgkmcnt(0)
	s_waitcnt lgkmcnt(0)
	v_mfma_f32_16x16x32_bf16 v[62:65], v[152:155], v[168:171], v[62:65]
	v_mfma_f32_16x16x32_bf16 v[58:61], v[160:163], v[168:171], v[58:61]
	v_mfma_f32_16x16x32_bf16 v[46:49], v[152:155], v[176:179], v[46:49]
	v_mfma_f32_16x16x32_bf16 v[42:45], v[160:163], v[176:179], v[42:45]
	v_mfma_f32_16x16x32_bf16 v[30:33], v[152:155], v[184:187], v[30:33]
	v_mfma_f32_16x16x32_bf16 v[26:29], v[160:163], v[184:187], v[26:29]
	v_mfma_f32_16x16x32_bf16 v[14:17], v[152:155], v[192:195], v[14:17]
	v_mfma_f32_16x16x32_bf16 v[10:13], v[160:163], v[192:195], v[10:13]
	v_mfma_f32_16x16x32_bf16 v[62:65], v[156:159], v[172:175], v[62:65]
	v_mfma_f32_16x16x32_bf16 v[58:61], v[164:167], v[172:175], v[58:61]
	v_mfma_f32_16x16x32_bf16 v[46:49], v[156:159], v[180:183], v[46:49]
	v_mfma_f32_16x16x32_bf16 v[42:45], v[164:167], v[180:183], v[42:45]
	v_mfma_f32_16x16x32_bf16 v[30:33], v[156:159], v[188:191], v[30:33]
	v_mfma_f32_16x16x32_bf16 v[26:29], v[164:167], v[188:191], v[26:29]
	v_mfma_f32_16x16x32_bf16 v[14:17], v[156:159], v[196:199], v[14:17]
	v_mfma_f32_16x16x32_bf16 v[10:13], v[164:167], v[196:199], v[10:13]
	s_barrier
	s_mov_b32 m0, s77
	v_lshl_add_u64 v[152:153], s[40:41], 0, v[134:135]
	global_load_lds_dwordx4 v[152:153], off
	v_lshl_add_u64 v[152:153], s[40:41], 0, v[130:131]
	s_mov_b32 m0, s1
	s_nop 0
	global_load_lds_dwordx4 v[152:153], off
	s_waitcnt vmcnt(10)
	s_barrier
	v_mfma_f32_16x16x32_bf16 v[54:57], v[200:203], v[168:171], v[54:57]
	v_mfma_f32_16x16x32_bf16 v[50:53], v[208:211], v[168:171], v[50:53]
	v_mfma_f32_16x16x32_bf16 v[38:41], v[200:203], v[176:179], v[38:41]
	v_mfma_f32_16x16x32_bf16 v[34:37], v[208:211], v[176:179], v[34:37]
	v_mfma_f32_16x16x32_bf16 v[22:25], v[200:203], v[184:187], v[22:25]
	v_mfma_f32_16x16x32_bf16 v[18:21], v[208:211], v[184:187], v[18:21]
	v_mfma_f32_16x16x32_bf16 v[6:9], v[200:203], v[192:195], v[6:9]
	v_mfma_f32_16x16x32_bf16 v[2:5], v[208:211], v[192:195], v[2:5]
	v_mfma_f32_16x16x32_bf16 v[54:57], v[204:207], v[172:175], v[54:57]
	v_mfma_f32_16x16x32_bf16 v[50:53], v[212:215], v[172:175], v[50:53]
	v_mfma_f32_16x16x32_bf16 v[38:41], v[204:207], v[180:183], v[38:41]
	v_mfma_f32_16x16x32_bf16 v[34:37], v[212:215], v[180:183], v[34:37]
	v_mfma_f32_16x16x32_bf16 v[22:25], v[204:207], v[188:191], v[22:25]
	v_mfma_f32_16x16x32_bf16 v[18:21], v[212:215], v[188:191], v[18:21]
	v_mfma_f32_16x16x32_bf16 v[6:9], v[204:207], v[196:199], v[6:9]
	v_mfma_f32_16x16x32_bf16 v[2:5], v[212:215], v[196:199], v[2:5]
	v_add_u32_e32 v151, s73, v146
	s_barrier
	ds_read_b128 v[152:155], v151
	ds_read_b128 v[156:159], v151 offset:1024
	ds_read_b128 v[160:163], v151 offset:2048
	ds_read_b128 v[164:167], v151 offset:3072
	s_mov_b32 m0, s49
	v_lshl_add_u64 v[200:201], s[38:39], 0, v[136:137]
	ds_read_b128 v[168:171], v148 offset:32768
	ds_read_b128 v[172:175], v148 offset:33792
	ds_read_b128 v[176:179], v148 offset:34816
	ds_read_b128 v[180:183], v148 offset:35840
	ds_read_b128 v[184:187], v148 offset:36864
	ds_read_b128 v[188:191], v148 offset:37888
	ds_read_b128 v[192:195], v148 offset:38912
	ds_read_b128 v[196:199], v148 offset:39936
	global_load_lds_dwordx4 v[200:201], off
	v_lshl_add_u64 v[200:201], s[38:39], 0, v[132:133]
	s_mov_b32 m0, s50
	s_nop 0
	global_load_lds_dwordx4 v[200:201], off
	s_waitcnt lgkmcnt(8)
	s_waitcnt vmcnt(10)
	s_barrier
	s_waitcnt lgkmcnt(0)
	s_waitcnt lgkmcnt(0)
	v_mfma_f32_16x16x32_bf16 v[126:129], v[152:155], v[168:171], v[126:129]
	v_mfma_f32_16x16x32_bf16 v[122:125], v[160:163], v[168:171], v[122:125]
	v_mfma_f32_16x16x32_bf16 v[110:113], v[152:155], v[176:179], v[110:113]
	v_mfma_f32_16x16x32_bf16 v[106:109], v[160:163], v[176:179], v[106:109]
	v_mfma_f32_16x16x32_bf16 v[94:97], v[152:155], v[184:187], v[94:97]
	v_mfma_f32_16x16x32_bf16 v[90:93], v[160:163], v[184:187], v[90:93]
	v_mfma_f32_16x16x32_bf16 v[78:81], v[152:155], v[192:195], v[78:81]
	v_mfma_f32_16x16x32_bf16 v[74:77], v[160:163], v[192:195], v[74:77]
	v_mfma_f32_16x16x32_bf16 v[126:129], v[156:159], v[172:175], v[126:129]
	v_mfma_f32_16x16x32_bf16 v[122:125], v[164:167], v[172:175], v[122:125]
	v_mfma_f32_16x16x32_bf16 v[110:113], v[156:159], v[180:183], v[110:113]
	v_mfma_f32_16x16x32_bf16 v[106:109], v[164:167], v[180:183], v[106:109]
	v_mfma_f32_16x16x32_bf16 v[94:97], v[156:159], v[188:191], v[94:97]
	v_mfma_f32_16x16x32_bf16 v[90:93], v[164:167], v[188:191], v[90:93]
	v_mfma_f32_16x16x32_bf16 v[78:81], v[156:159], v[196:199], v[78:81]
	v_mfma_f32_16x16x32_bf16 v[74:77], v[164:167], v[196:199], v[74:77]
	s_barrier
	s_mov_b32 m0, s72
	v_add_u32_e32 v151, s69, v146
	v_lshl_add_u64 v[142:143], v[142:143], 0, s[16:17]
	ds_read_b128 v[200:203], v151
	ds_read_b128 v[204:207], v151 offset:1024
	ds_read_b128 v[208:211], v151 offset:2048
	ds_read_b128 v[212:215], v151 offset:3072
	global_load_lds_dwordx4 v[142:143], off
	v_lshl_add_u64 v[142:143], v[216:217], 0, s[16:17]
	s_mov_b32 m0, s67
	s_nop 0
	global_load_lds_dwordx4 v[142:143], off
	s_waitcnt vmcnt(10)
	s_barrier
	s_waitcnt lgkmcnt(0)
	s_waitcnt lgkmcnt(0)
	v_mfma_f32_16x16x32_bf16 v[118:121], v[200:203], v[168:171], v[118:121]
	v_mfma_f32_16x16x32_bf16 v[114:117], v[208:211], v[168:171], v[114:117]
	v_mfma_f32_16x16x32_bf16 v[102:105], v[200:203], v[176:179], v[102:105]
	v_mfma_f32_16x16x32_bf16 v[98:101], v[208:211], v[176:179], v[98:101]
	v_mfma_f32_16x16x32_bf16 v[86:89], v[200:203], v[184:187], v[86:89]
	v_mfma_f32_16x16x32_bf16 v[82:85], v[208:211], v[184:187], v[82:85]
	v_mfma_f32_16x16x32_bf16 v[70:73], v[200:203], v[192:195], v[70:73]
	v_mfma_f32_16x16x32_bf16 v[66:69], v[208:211], v[192:195], v[66:69]
	v_mfma_f32_16x16x32_bf16 v[118:121], v[204:207], v[172:175], v[118:121]
	v_mfma_f32_16x16x32_bf16 v[114:117], v[212:215], v[172:175], v[114:117]
	v_mfma_f32_16x16x32_bf16 v[102:105], v[204:207], v[180:183], v[102:105]
	v_mfma_f32_16x16x32_bf16 v[98:101], v[212:215], v[180:183], v[98:101]
	v_mfma_f32_16x16x32_bf16 v[86:89], v[204:207], v[188:191], v[86:89]
	v_mfma_f32_16x16x32_bf16 v[82:85], v[212:215], v[188:191], v[82:85]
	v_mfma_f32_16x16x32_bf16 v[70:73], v[204:207], v[196:199], v[70:73]
	v_mfma_f32_16x16x32_bf16 v[66:69], v[212:215], v[196:199], v[66:69]
	s_mov_b32 m0, s56
	v_lshl_add_u64 v[142:143], v[218:219], 0, s[16:17]
	s_barrier
	ds_read_b128 v[168:171], v148 offset:49152
	ds_read_b128 v[172:175], v148 offset:50176
	ds_read_b128 v[176:179], v148 offset:51200
	ds_read_b128 v[180:183], v148 offset:52224
	ds_read_b128 v[184:187], v148 offset:53248
	ds_read_b128 v[188:191], v148 offset:54272
	ds_read_b128 v[192:195], v148 offset:55296
	ds_read_b128 v[196:199], v148 offset:56320
	global_load_lds_dwordx4 v[142:143], off
	v_lshl_add_u64 v[142:143], v[220:221], 0, s[16:17]
	s_mov_b32 m0, s57
	s_nop 0
	global_load_lds_dwordx4 v[142:143], off
	s_waitcnt vmcnt(10)
	s_barrier
	s_waitcnt lgkmcnt(0)
	s_waitcnt lgkmcnt(0)
	v_mfma_f32_16x16x32_bf16 v[62:65], v[152:155], v[168:171], v[62:65]
	v_mfma_f32_16x16x32_bf16 v[58:61], v[160:163], v[168:171], v[58:61]
	v_mfma_f32_16x16x32_bf16 v[46:49], v[152:155], v[176:179], v[46:49]
	v_mfma_f32_16x16x32_bf16 v[42:45], v[160:163], v[176:179], v[42:45]
	v_mfma_f32_16x16x32_bf16 v[30:33], v[152:155], v[184:187], v[30:33]
	v_mfma_f32_16x16x32_bf16 v[26:29], v[160:163], v[184:187], v[26:29]
	v_mfma_f32_16x16x32_bf16 v[14:17], v[152:155], v[192:195], v[14:17]
	v_mfma_f32_16x16x32_bf16 v[10:13], v[160:163], v[192:195], v[10:13]
	v_mfma_f32_16x16x32_bf16 v[62:65], v[156:159], v[172:175], v[62:65]
	v_mfma_f32_16x16x32_bf16 v[58:61], v[164:167], v[172:175], v[58:61]
	v_mfma_f32_16x16x32_bf16 v[46:49], v[156:159], v[180:183], v[46:49]
	v_mfma_f32_16x16x32_bf16 v[42:45], v[164:167], v[180:183], v[42:45]
	v_mfma_f32_16x16x32_bf16 v[30:33], v[156:159], v[188:191], v[30:33]
	v_mfma_f32_16x16x32_bf16 v[26:29], v[164:167], v[188:191], v[26:29]
	v_mfma_f32_16x16x32_bf16 v[14:17], v[156:159], v[196:199], v[14:17]
	v_mfma_f32_16x16x32_bf16 v[10:13], v[164:167], v[196:199], v[10:13]
	s_barrier
	s_mov_b32 m0, s65
	v_lshl_add_u64 v[142:143], s[36:37], 0, v[134:135]
	global_load_lds_dwordx4 v[142:143], off
	v_lshl_add_u64 v[142:143], s[36:37], 0, v[130:131]
	s_mov_b32 m0, s64
	s_nop 0
	global_load_lds_dwordx4 v[142:143], off
	s_waitcnt vmcnt(10)
	s_barrier
	v_mfma_f32_16x16x32_bf16 v[54:57], v[200:203], v[168:171], v[54:57]
	v_mfma_f32_16x16x32_bf16 v[50:53], v[208:211], v[168:171], v[50:53]
	v_mfma_f32_16x16x32_bf16 v[38:41], v[200:203], v[176:179], v[38:41]
	v_mfma_f32_16x16x32_bf16 v[34:37], v[208:211], v[176:179], v[34:37]
	v_mfma_f32_16x16x32_bf16 v[22:25], v[200:203], v[184:187], v[22:25]
	v_mfma_f32_16x16x32_bf16 v[18:21], v[208:211], v[184:187], v[18:21]
	v_mfma_f32_16x16x32_bf16 v[6:9], v[200:203], v[192:195], v[6:9]
	v_mfma_f32_16x16x32_bf16 v[2:5], v[208:211], v[192:195], v[2:5]
	v_mfma_f32_16x16x32_bf16 v[54:57], v[204:207], v[172:175], v[54:57]
	v_mfma_f32_16x16x32_bf16 v[50:53], v[212:215], v[172:175], v[50:53]
	v_mfma_f32_16x16x32_bf16 v[38:41], v[204:207], v[180:183], v[38:41]
	v_mfma_f32_16x16x32_bf16 v[34:37], v[212:215], v[180:183], v[34:37]
	v_mfma_f32_16x16x32_bf16 v[22:25], v[204:207], v[188:191], v[22:25]
	v_mfma_f32_16x16x32_bf16 v[18:21], v[212:215], v[188:191], v[18:21]
	v_mfma_f32_16x16x32_bf16 v[6:9], v[204:207], v[196:199], v[6:9]
	v_mfma_f32_16x16x32_bf16 v[2:5], v[212:215], v[196:199], v[2:5]
	s_movk_i32 s38, 0x100
	s_andn2_b64 vcc, exec, s[34:35]
	s_mov_b64 s[36:37], -1
	s_mov_b64 s[34:35], 0
	s_barrier
	s_cbranch_vccz .LBB0_2344
	s_lshl_b32 s0, s26, 8
	v_mov_b32_e32 v143, v144
	s_add_i32 s0, s0, s53
	v_mov_b32_e32 v142, v145
	v_add_u32_e32 v151, s0, v143
	v_mov_b32_e32 v154, v151
	v_max_f32_e32 v126, v126, v126
	v_ashrrev_i32_e32 v152, 8, v154
	v_and_b32_e32 v152, -8, v152
	v_add_u32_e32 v152, s55, v152
	v_ashrrev_i32_e32 v153, 31, v152
	v_lshlrev_b64 v[152:153], 11, v[152:153]
	v_and_or_b32 v152, v154, s60, v152
	v_med3_f32 v154, v126, s61, v150
	v_max_f32_e32 v126, v127, v127
	v_med3_f32 v127, v126, s61, v150
	v_mov_b32_e32 v126, 0
	v_cvt_pk_fp8_f32 v126, v154, v127
	v_max_f32_e32 v127, v128, v128
	v_max_f32_e32 v128, v129, v129
	v_med3_f32 v127, v127, s61, v150
	v_med3_f32 v128, v128, s61, v150
	v_max_f32_e32 v122, v122, v122
	v_max_f32_e32 v123, v123, v123
	v_cvt_pk_fp8_f32 v126, v127, v128 op_sel:[0,0,1]
	v_med3_f32 v122, v122, s61, v150
	v_med3_f32 v123, v123, s61, v150
	v_mov_b32_e32 v127, 0
	v_cvt_pk_fp8_f32 v127, v122, v123
	v_max_f32_e32 v122, v124, v124
	v_max_f32_e32 v123, v125, v125
	v_med3_f32 v122, v122, s61, v150
	v_med3_f32 v123, v123, s61, v150
	v_lshl_add_u32 v142, v142, 3, s54
	v_cvt_pk_fp8_f32 v127, v122, v123 op_sel:[0,0,1]
	v_mov_b64_e32 v[122:123], s[12:13]
	v_ashrrev_i32_e32 v143, 31, v142
	v_mad_u64_u32 v[124:125], s[0:1], v152, s51, v[122:123]
	v_cvt_pk_bf16_f32 v118, v118, v119
	v_cvt_pk_bf16_f32 v119, v120, v121
	v_cvt_pk_bf16_f32 v120, v114, v115
	v_lshlrev_b64 v[114:115], 8, v[152:153]
	v_mad_i32_i24 v125, v153, s51, v125
	v_cvt_pk_bf16_f32 v121, v116, v117
	v_lshl_add_u64 v[116:117], s[14:15], 0, v[114:115]
	v_lshlrev_b64 v[114:115], 1, v[142:143]
	v_lshl_add_u64 v[124:125], v[124:125], 0, v[142:143]
	v_lshl_add_u64 v[116:117], v[116:117], 0, v[114:115]
	global_store_dwordx2 v[124:125], v[126:127], off
	global_store_dwordx4 v[116:117], v[118:121], off
	v_max_f32_e32 v110, v110, v110
	v_max_f32_e32 v106, v106, v106
	v_add_u32_e32 v118, 16, v151
	v_max_f32_e32 v107, v107, v107
	v_ashrrev_i32_e32 v116, 8, v118
	v_and_b32_e32 v116, -8, v116
	v_add_u32_e32 v116, s55, v116
	v_ashrrev_i32_e32 v117, 31, v116
	v_lshlrev_b64 v[116:117], 11, v[116:117]
	v_and_or_b32 v116, v118, s60, v116
	v_med3_f32 v118, v110, s61, v150
	v_max_f32_e32 v110, v111, v111
	v_med3_f32 v111, v110, s61, v150
	v_mov_b32_e32 v110, 0
	v_cvt_pk_fp8_f32 v110, v118, v111
	v_max_f32_e32 v111, v112, v112
	v_max_f32_e32 v112, v113, v113
	v_med3_f32 v111, v111, s61, v150
	v_med3_f32 v112, v112, s61, v150
	v_cvt_pk_fp8_f32 v110, v111, v112 op_sel:[0,0,1]
	v_med3_f32 v106, v106, s61, v150
	v_med3_f32 v107, v107, s61, v150
	v_mov_b32_e32 v111, 0
	v_cvt_pk_fp8_f32 v111, v106, v107
	v_max_f32_e32 v106, v108, v108
	v_max_f32_e32 v107, v109, v109
	v_med3_f32 v106, v106, s61, v150
	v_med3_f32 v107, v107, s61, v150
	v_cvt_pk_fp8_f32 v111, v106, v107 op_sel:[0,0,1]
	v_mad_u64_u32 v[106:107], s[0:1], v116, s51, v[122:123]
	v_cvt_pk_bf16_f32 v102, v102, v103
	v_cvt_pk_bf16_f32 v103, v104, v105
	v_cvt_pk_bf16_f32 v104, v98, v99
	v_lshlrev_b64 v[98:99], 8, v[116:117]
	v_mad_i32_i24 v107, v117, s51, v107
	v_lshl_add_u64 v[98:99], s[14:15], 0, v[98:99]
	v_lshl_add_u64 v[106:107], v[106:107], 0, v[142:143]
	v_cvt_pk_bf16_f32 v105, v100, v101
	v_lshl_add_u64 v[98:99], v[98:99], 0, v[114:115]
	v_add_u32_e32 v100, 32, v151
	global_store_dwordx2 v[106:107], v[110:111], off
	global_store_dwordx4 v[98:99], v[102:105], off
	v_max_f32_e32 v94, v94, v94
	v_ashrrev_i32_e32 v98, 8, v100
	v_and_b32_e32 v98, -8, v98
	v_add_u32_e32 v98, s55, v98
	v_ashrrev_i32_e32 v99, 31, v98
	v_lshlrev_b64 v[98:99], 11, v[98:99]
	v_and_or_b32 v98, v100, s60, v98
	v_med3_f32 v100, v94, s61, v150
	v_max_f32_e32 v94, v95, v95
	v_med3_f32 v95, v94, s61, v150
	v_mov_b32_e32 v94, 0
	v_cvt_pk_fp8_f32 v94, v100, v95
	v_max_f32_e32 v95, v96, v96
	v_max_f32_e32 v96, v97, v97
	v_med3_f32 v95, v95, s61, v150
	v_med3_f32 v96, v96, s61, v150
	v_max_f32_e32 v90, v90, v90
	v_max_f32_e32 v91, v91, v91
	v_cvt_pk_fp8_f32 v94, v95, v96 op_sel:[0,0,1]
	v_med3_f32 v90, v90, s61, v150
	v_med3_f32 v91, v91, s61, v150
	v_mov_b32_e32 v95, 0
	v_cvt_pk_fp8_f32 v95, v90, v91
	v_max_f32_e32 v90, v92, v92
	v_max_f32_e32 v91, v93, v93
	v_med3_f32 v90, v90, s61, v150
	v_med3_f32 v91, v91, s61, v150
	v_cvt_pk_fp8_f32 v95, v90, v91 op_sel:[0,0,1]
	v_mad_u64_u32 v[90:91], s[0:1], v98, s51, v[122:123]
	v_cvt_pk_bf16_f32 v86, v86, v87
	v_cvt_pk_bf16_f32 v87, v88, v89
	v_cvt_pk_bf16_f32 v88, v82, v83
	v_lshlrev_b64 v[82:83], 8, v[98:99]
	v_mad_i32_i24 v91, v99, s51, v91
	v_lshl_add_u64 v[82:83], s[14:15], 0, v[82:83]
	v_lshl_add_u64 v[90:91], v[90:91], 0, v[142:143]
	v_cvt_pk_bf16_f32 v89, v84, v85
	v_lshl_add_u64 v[82:83], v[82:83], 0, v[114:115]
	v_add_u32_e32 v84, 48, v151
	global_store_dwordx2 v[90:91], v[94:95], off
	global_store_dwordx4 v[82:83], v[86:89], off
	v_max_f32_e32 v78, v78, v78
	v_ashrrev_i32_e32 v82, 8, v84
	v_and_b32_e32 v82, -8, v82
	v_add_u32_e32 v82, s55, v82
	v_ashrrev_i32_e32 v83, 31, v82
	v_lshlrev_b64 v[82:83], 11, v[82:83]
	v_and_or_b32 v82, v84, s60, v82
	v_med3_f32 v84, v78, s61, v150
	v_max_f32_e32 v78, v79, v79
	v_med3_f32 v79, v78, s61, v150
	v_mov_b32_e32 v78, 0
	v_cvt_pk_fp8_f32 v78, v84, v79
	v_max_f32_e32 v79, v80, v80
	v_max_f32_e32 v80, v81, v81
	v_med3_f32 v79, v79, s61, v150
	v_med3_f32 v80, v80, s61, v150
	v_max_f32_e32 v74, v74, v74
	v_max_f32_e32 v75, v75, v75
	v_cvt_pk_fp8_f32 v78, v79, v80 op_sel:[0,0,1]
	v_med3_f32 v74, v74, s61, v150
	v_med3_f32 v75, v75, s61, v150
	v_mov_b32_e32 v79, 0
	v_cvt_pk_fp8_f32 v79, v74, v75
	v_max_f32_e32 v74, v76, v76
	v_max_f32_e32 v75, v77, v77
	v_med3_f32 v74, v74, s61, v150
	v_med3_f32 v75, v75, s61, v150
	v_cvt_pk_fp8_f32 v79, v74, v75 op_sel:[0,0,1]
	v_mad_u64_u32 v[74:75], s[0:1], v82, s51, v[122:123]
	v_cvt_pk_bf16_f32 v70, v70, v71
	v_cvt_pk_bf16_f32 v71, v72, v73
	v_cvt_pk_bf16_f32 v72, v66, v67
	v_lshlrev_b64 v[66:67], 8, v[82:83]
	v_mad_i32_i24 v75, v83, s51, v75
	v_lshl_add_u64 v[66:67], s[14:15], 0, v[66:67]
	v_lshl_add_u64 v[74:75], v[74:75], 0, v[142:143]
	v_cvt_pk_bf16_f32 v73, v68, v69
	v_lshl_add_u64 v[66:67], v[66:67], 0, v[114:115]
	v_add_u32_e32 v68, 0x80, v151
	global_store_dwordx2 v[74:75], v[78:79], off
	global_store_dwordx4 v[66:67], v[70:73], off
	v_max_f32_e32 v62, v62, v62
	v_ashrrev_i32_e32 v66, 8, v68
	v_and_b32_e32 v66, -8, v66
	v_add_u32_e32 v66, s55, v66
	v_ashrrev_i32_e32 v67, 31, v66
	v_lshlrev_b64 v[66:67], 11, v[66:67]
	v_and_or_b32 v66, v68, s60, v66
	v_med3_f32 v68, v62, s61, v150
	v_max_f32_e32 v62, v63, v63
	v_med3_f32 v63, v62, s61, v150
	v_mov_b32_e32 v62, 0
	v_cvt_pk_fp8_f32 v62, v68, v63
	v_max_f32_e32 v63, v64, v64
	v_max_f32_e32 v64, v65, v65
	v_med3_f32 v63, v63, s61, v150
	v_med3_f32 v64, v64, s61, v150
	v_max_f32_e32 v58, v58, v58
	v_max_f32_e32 v59, v59, v59
	v_cvt_pk_fp8_f32 v62, v63, v64 op_sel:[0,0,1]
	v_med3_f32 v58, v58, s61, v150
	v_med3_f32 v59, v59, s61, v150
	v_mov_b32_e32 v63, 0
	v_cvt_pk_fp8_f32 v63, v58, v59
	v_max_f32_e32 v58, v60, v60
	v_max_f32_e32 v59, v61, v61
	v_med3_f32 v58, v58, s61, v150
	v_med3_f32 v59, v59, s61, v150
	v_cvt_pk_fp8_f32 v63, v58, v59 op_sel:[0,0,1]
	v_mad_u64_u32 v[58:59], s[0:1], v66, s51, v[122:123]
	v_cvt_pk_bf16_f32 v54, v54, v55
	v_cvt_pk_bf16_f32 v55, v56, v57
	v_cvt_pk_bf16_f32 v56, v50, v51
	v_lshlrev_b64 v[50:51], 8, v[66:67]
	v_mad_i32_i24 v59, v67, s51, v59
	v_lshl_add_u64 v[50:51], s[14:15], 0, v[50:51]
	v_lshl_add_u64 v[58:59], v[58:59], 0, v[142:143]
	v_cvt_pk_bf16_f32 v57, v52, v53
	v_lshl_add_u64 v[50:51], v[50:51], 0, v[114:115]
	v_add_u32_e32 v52, 0x90, v151
	global_store_dwordx2 v[58:59], v[62:63], off
	global_store_dwordx4 v[50:51], v[54:57], off
	v_max_f32_e32 v46, v46, v46
	v_ashrrev_i32_e32 v50, 8, v52
	v_and_b32_e32 v50, -8, v50
	v_add_u32_e32 v50, s55, v50
	v_ashrrev_i32_e32 v51, 31, v50
	v_lshlrev_b64 v[50:51], 11, v[50:51]
	v_and_or_b32 v50, v52, s60, v50
	v_med3_f32 v52, v46, s61, v150
	v_max_f32_e32 v46, v47, v47
	v_med3_f32 v47, v46, s61, v150
	v_mov_b32_e32 v46, 0
	v_cvt_pk_fp8_f32 v46, v52, v47
	v_max_f32_e32 v47, v48, v48
	v_max_f32_e32 v48, v49, v49
	v_med3_f32 v47, v47, s61, v150
	v_med3_f32 v48, v48, s61, v150
	v_max_f32_e32 v42, v42, v42
	v_max_f32_e32 v43, v43, v43
	v_cvt_pk_fp8_f32 v46, v47, v48 op_sel:[0,0,1]
	v_med3_f32 v42, v42, s61, v150
	v_med3_f32 v43, v43, s61, v150
	v_mov_b32_e32 v47, 0
	v_cvt_pk_fp8_f32 v47, v42, v43
	v_max_f32_e32 v42, v44, v44
	v_max_f32_e32 v43, v45, v45
	v_med3_f32 v42, v42, s61, v150
	v_med3_f32 v43, v43, s61, v150
	v_cvt_pk_fp8_f32 v47, v42, v43 op_sel:[0,0,1]
	v_mad_u64_u32 v[42:43], s[0:1], v50, s51, v[122:123]
	v_cvt_pk_bf16_f32 v38, v38, v39
	v_cvt_pk_bf16_f32 v39, v40, v41
	v_cvt_pk_bf16_f32 v40, v34, v35
	v_lshlrev_b64 v[34:35], 8, v[50:51]
	v_mad_i32_i24 v43, v51, s51, v43
	v_lshl_add_u64 v[34:35], s[14:15], 0, v[34:35]
	v_lshl_add_u64 v[42:43], v[42:43], 0, v[142:143]
	v_cvt_pk_bf16_f32 v41, v36, v37
	v_lshl_add_u64 v[34:35], v[34:35], 0, v[114:115]
	v_add_u32_e32 v36, 0xa0, v151
	global_store_dwordx2 v[42:43], v[46:47], off
	global_store_dwordx4 v[34:35], v[38:41], off
	v_max_f32_e32 v30, v30, v30
	v_ashrrev_i32_e32 v34, 8, v36
	v_and_b32_e32 v34, -8, v34
	v_add_u32_e32 v34, s55, v34
	v_ashrrev_i32_e32 v35, 31, v34
	v_lshlrev_b64 v[34:35], 11, v[34:35]
	v_and_or_b32 v34, v36, s60, v34
	v_med3_f32 v36, v30, s61, v150
	v_max_f32_e32 v30, v31, v31
	v_med3_f32 v31, v30, s61, v150
	v_mov_b32_e32 v30, 0
	v_cvt_pk_fp8_f32 v30, v36, v31
	v_max_f32_e32 v31, v32, v32
	v_max_f32_e32 v32, v33, v33
	v_med3_f32 v31, v31, s61, v150
	v_med3_f32 v32, v32, s61, v150
	v_max_f32_e32 v26, v26, v26
	v_max_f32_e32 v27, v27, v27
	v_cvt_pk_fp8_f32 v30, v31, v32 op_sel:[0,0,1]
	v_med3_f32 v26, v26, s61, v150
	v_med3_f32 v27, v27, s61, v150
	v_mov_b32_e32 v31, 0
	v_cvt_pk_fp8_f32 v31, v26, v27
	v_max_f32_e32 v26, v28, v28
	v_max_f32_e32 v27, v29, v29
	v_med3_f32 v26, v26, s61, v150
	v_med3_f32 v27, v27, s61, v150
	v_cvt_pk_fp8_f32 v31, v26, v27 op_sel:[0,0,1]
	v_mad_u64_u32 v[26:27], s[0:1], v34, s51, v[122:123]
	v_cvt_pk_bf16_f32 v22, v22, v23
	v_cvt_pk_bf16_f32 v23, v24, v25
	v_cvt_pk_bf16_f32 v24, v18, v19
	v_lshlrev_b64 v[18:19], 8, v[34:35]
	v_mad_i32_i24 v27, v35, s51, v27
	v_lshl_add_u64 v[18:19], s[14:15], 0, v[18:19]
	v_lshl_add_u64 v[26:27], v[26:27], 0, v[142:143]
	v_cvt_pk_bf16_f32 v25, v20, v21
	v_lshl_add_u64 v[18:19], v[18:19], 0, v[114:115]
	v_add_u32_e32 v20, 0xb0, v151
	global_store_dwordx2 v[26:27], v[30:31], off
	global_store_dwordx4 v[18:19], v[22:25], off
	v_max_f32_e32 v14, v14, v14
	v_ashrrev_i32_e32 v18, 8, v20
	v_and_b32_e32 v18, -8, v18
	v_add_u32_e32 v18, s55, v18
	v_ashrrev_i32_e32 v19, 31, v18
	v_lshlrev_b64 v[18:19], 11, v[18:19]
	v_and_or_b32 v18, v20, s60, v18
	v_med3_f32 v20, v14, s61, v150
	v_max_f32_e32 v14, v15, v15
	v_med3_f32 v15, v14, s61, v150
	v_mov_b32_e32 v14, 0
	v_cvt_pk_fp8_f32 v14, v20, v15
	v_max_f32_e32 v15, v16, v16
	v_max_f32_e32 v16, v17, v17
	v_med3_f32 v15, v15, s61, v150
	v_med3_f32 v16, v16, s61, v150
	v_max_f32_e32 v10, v10, v10
	v_max_f32_e32 v11, v11, v11
	v_cvt_pk_fp8_f32 v14, v15, v16 op_sel:[0,0,1]
	v_med3_f32 v10, v10, s61, v150
	v_med3_f32 v11, v11, s61, v150
	v_mov_b32_e32 v15, 0
	v_cvt_pk_fp8_f32 v15, v10, v11
	v_max_f32_e32 v10, v12, v12
	v_max_f32_e32 v11, v13, v13
	v_med3_f32 v10, v10, s61, v150
	v_med3_f32 v11, v11, s61, v150
	v_cvt_pk_fp8_f32 v15, v10, v11 op_sel:[0,0,1]
	v_mad_u64_u32 v[10:11], s[0:1], v18, s51, v[122:123]
	v_cvt_pk_bf16_f32 v6, v6, v7
	v_cvt_pk_bf16_f32 v7, v8, v9
	v_cvt_pk_bf16_f32 v8, v2, v3
	v_lshlrev_b64 v[2:3], 8, v[18:19]
	v_mad_i32_i24 v11, v19, s51, v11
	v_lshl_add_u64 v[2:3], s[14:15], 0, v[2:3]
	v_readlane_b32 s72, v254, 2
	v_lshl_add_u64 v[10:11], v[10:11], 0, v[142:143]
	v_cvt_pk_bf16_f32 v9, v4, v5
	v_lshl_add_u64 v[2:3], v[2:3], 0, v[114:115]
	s_and_b64 vcc, exec, s[10:11]
	s_mov_b32 s55, s18
	s_mov_b32 s26, s20
	s_mov_b64 s[28:29], s[24:25]
	s_mov_b64 s[30:31], s[22:23]
	v_readlane_b32 s73, v254, 3
	global_store_dwordx2 v[10:11], v[14:15], off
	global_store_dwordx4 v[2:3], v[6:9], off
	s_cbranch_vccz .LBB0_2337
	s_waitcnt vmcnt(0)
	s_cmpk_gt_u32 s5, 0xff
	s_cbranch_scc1 .LBB0_2348
	s_barrier

.LBB0_2404:
	s_or_b64 exec, exec, s[12:13]
	s_waitcnt lgkmcnt(0)
	v_add_u32_e32 v2, v157, v174
	ds_read_b128 v[68:71], v2 offset:57344
	ds_read_b128 v[72:75], v2 offset:57376
	s_lshl_b64 s[0:1], s[40:41], 11
	s_add_u32 s0, s53, s0
	s_addc_u32 s1, s54, s1
	s_waitcnt lgkmcnt(1)
	v_rcp_f32_e32 v76, v68
	v_rcp_f32_e32 v77, v69
	v_rcp_f32_e32 v78, v70
	v_rcp_f32_e32 v79, v71
	ds_read_b128 v[68:71], v2 offset:57408
	s_lshl_b32 s10, s60, 8
	s_add_u32 s0, s0, s10
	v_ashrrev_i32_e32 v157, 31, v156
	s_addc_u32 s1, s1, 0
	s_waitcnt lgkmcnt(1)
	v_rcp_f32_e32 v80, v72
	v_rcp_f32_e32 v81, v73
	v_rcp_f32_e32 v82, v74
	v_rcp_f32_e32 v83, v75
	ds_read_b128 v[72:75], v2 offset:57440
	s_waitcnt lgkmcnt(1)
	v_rcp_f32_e32 v84, v68
	v_rcp_f32_e32 v85, v69
	v_lshlrev_b64 v[68:69], 11, v[156:157]
	v_lshl_add_u64 v[68:69], s[0:1], 0, v[68:69]
	v_lshlrev_b32_e32 v2, 1, v172
	v_rcp_f32_e32 v86, v70
	v_rcp_f32_e32 v87, v71
	v_lshlrev_b32_e32 v70, 13, v173
	v_lshl_add_u64 v[68:69], v[68:69], 0, v[2:3]
	v_mov_b32_e32 v71, v3
	v_mul_f32_e32 v2, v52, v76
	v_lshl_add_u64 v[68:69], v[68:69], 0, v[70:71]
	v_cvt_pk_bf16_f32 v2, v2, s0
	global_store_short v[68:69], v2, off
	v_mul_f32_e32 v2, v36, v76
	v_cvt_pk_bf16_f32 v2, v2, s0
	global_store_short v[68:69], v2, off offset:64
	v_mul_f32_e32 v2, v20, v76
	v_cvt_pk_bf16_f32 v2, v2, s0
	global_store_short v[68:69], v2, off offset:128
	v_mul_f32_e32 v2, v4, v76
	v_cvt_pk_bf16_f32 v2, v2, s0
	global_store_short v[68:69], v2, off offset:192
	v_mul_f32_e32 v2, v53, v77
	v_cvt_pk_bf16_f32 v2, v2, s0
	global_store_short v[68:69], v2, off offset:2048
	v_mul_f32_e32 v2, v37, v77
	v_cvt_pk_bf16_f32 v2, v2, s0
	global_store_short v[68:69], v2, off offset:2112
	v_mul_f32_e32 v2, v21, v77
	v_cvt_pk_bf16_f32 v2, v2, s0
	global_store_short v[68:69], v2, off offset:2176
	v_mul_f32_e32 v2, v5, v77
	v_cvt_pk_bf16_f32 v2, v2, s0
	global_store_short v[68:69], v2, off offset:2240
	v_mul_f32_e32 v2, v54, v78
	v_cvt_pk_bf16_f32 v2, v2, s0
	s_movk_i32 s0, 0x1000
	v_add_co_u32_e32 v4, vcc, s0, v68
	s_waitcnt lgkmcnt(0)
	v_rcp_f32_e32 v72, v72
	v_addc_co_u32_e32 v5, vcc, 0, v69, vcc
	global_store_short v[4:5], v2, off
	v_mul_f32_e32 v2, v38, v78
	v_cvt_pk_bf16_f32 v2, v2, s0
	global_store_short v[4:5], v2, off offset:64
	v_mul_f32_e32 v2, v22, v78
	v_cvt_pk_bf16_f32 v2, v2, s0
	global_store_short v[4:5], v2, off offset:128
	v_mul_f32_e32 v2, v6, v78
	v_cvt_pk_bf16_f32 v2, v2, s0
	global_store_short v[4:5], v2, off offset:192
	v_mul_f32_e32 v2, v55, v79
	v_cvt_pk_bf16_f32 v2, v2, s0
	global_store_short v[4:5], v2, off offset:2048
	v_mul_f32_e32 v2, v39, v79
	v_cvt_pk_bf16_f32 v2, v2, s0
	global_store_short v[4:5], v2, off offset:2112
	v_mul_f32_e32 v2, v23, v79
	v_cvt_pk_bf16_f32 v2, v2, s0
	global_store_short v[4:5], v2, off offset:2176
	v_mul_f32_e32 v2, v7, v79
	v_cvt_pk_bf16_f32 v2, v2, s0
	global_store_short v[4:5], v2, off offset:2240
	v_mul_f32_e32 v2, v56, v80
	v_add_co_u32_e32 v4, vcc, s59, v68
	v_cvt_pk_bf16_f32 v2, v2, s0
	s_nop 0
	v_addc_co_u32_e32 v5, vcc, 0, v69, vcc
	global_store_short v[4:5], v2, off
	v_mul_f32_e32 v2, v40, v80
	v_cvt_pk_bf16_f32 v2, v2, s0
	global_store_short v[4:5], v2, off offset:64
	v_mul_f32_e32 v2, v24, v80
	v_cvt_pk_bf16_f32 v2, v2, s0
	global_store_short v[4:5], v2, off offset:128
	v_mul_f32_e32 v2, v8, v80
	v_cvt_pk_bf16_f32 v2, v2, s0
	global_store_short v[4:5], v2, off offset:192
	v_mul_f32_e32 v2, v57, v81
	v_cvt_pk_bf16_f32 v2, v2, s0
	global_store_short v[4:5], v2, off offset:2048
	v_mul_f32_e32 v2, v41, v81
	v_cvt_pk_bf16_f32 v2, v2, s0
	global_store_short v[4:5], v2, off offset:2112
	v_mul_f32_e32 v2, v25, v81
	v_cvt_pk_bf16_f32 v2, v2, s0
	global_store_short v[4:5], v2, off offset:2176
	v_mul_f32_e32 v2, v9, v81
	v_cvt_pk_bf16_f32 v2, v2, s0
	global_store_short v[4:5], v2, off offset:2240
	v_mul_f32_e32 v2, v58, v82
	v_cvt_pk_bf16_f32 v2, v2, s0
	s_movk_i32 s0, 0x5000
	v_add_co_u32_e32 v4, vcc, s0, v68
	v_rcp_f32_e32 v73, v73
	s_nop 0
	v_addc_co_u32_e32 v5, vcc, 0, v69, vcc
	global_store_short v[4:5], v2, off
	v_mul_f32_e32 v2, v42, v82
	v_cvt_pk_bf16_f32 v2, v2, s0
	global_store_short v[4:5], v2, off offset:64
	v_mul_f32_e32 v2, v26, v82
	v_cvt_pk_bf16_f32 v2, v2, s0
	global_store_short v[4:5], v2, off offset:128
	v_mul_f32_e32 v2, v10, v82
	v_cvt_pk_bf16_f32 v2, v2, s0
	global_store_short v[4:5], v2, off offset:192
	v_mul_f32_e32 v2, v59, v83
	v_cvt_pk_bf16_f32 v2, v2, s0
	global_store_short v[4:5], v2, off offset:2048
	v_mul_f32_e32 v2, v43, v83
	v_cvt_pk_bf16_f32 v2, v2, s0
	global_store_short v[4:5], v2, off offset:2112
	v_mul_f32_e32 v2, v27, v83
	v_cvt_pk_bf16_f32 v2, v2, s0
	global_store_short v[4:5], v2, off offset:2176
	v_mul_f32_e32 v2, v11, v83
	v_cvt_pk_bf16_f32 v2, v2, s0
	global_store_short v[4:5], v2, off offset:2240
	v_mul_f32_e32 v2, v60, v84
	v_cvt_pk_bf16_f32 v2, v2, s0
	s_mov_b32 s0, 0x8000
	v_add_co_u32_e32 v4, vcc, s0, v68
	v_rcp_f32_e32 v74, v74
	s_nop 0
	v_addc_co_u32_e32 v5, vcc, 0, v69, vcc
	global_store_short v[4:5], v2, off
	v_mul_f32_e32 v2, v44, v84
	v_cvt_pk_bf16_f32 v2, v2, s0
	global_store_short v[4:5], v2, off offset:64
	v_mul_f32_e32 v2, v28, v84
	v_cvt_pk_bf16_f32 v2, v2, s0
	global_store_short v[4:5], v2, off offset:128
	v_mul_f32_e32 v2, v12, v84
	v_cvt_pk_bf16_f32 v2, v2, s0
	global_store_short v[4:5], v2, off offset:192
	v_mul_f32_e32 v2, v61, v85
	v_cvt_pk_bf16_f32 v2, v2, s0
	global_store_short v[4:5], v2, off offset:2048
	v_mul_f32_e32 v2, v45, v85
	v_cvt_pk_bf16_f32 v2, v2, s0
	global_store_short v[4:5], v2, off offset:2112
	v_mul_f32_e32 v2, v29, v85
	v_cvt_pk_bf16_f32 v2, v2, s0
	global_store_short v[4:5], v2, off offset:2176
	v_mul_f32_e32 v2, v13, v85
	v_cvt_pk_bf16_f32 v2, v2, s0
	global_store_short v[4:5], v2, off offset:2240
	v_mul_f32_e32 v2, v62, v86
	v_cvt_pk_bf16_f32 v2, v2, s0
	s_mov_b32 s0, 0x9000
	v_add_co_u32_e32 v4, vcc, s0, v68
	v_rcp_f32_e32 v75, v75
	s_nop 0
	v_addc_co_u32_e32 v5, vcc, 0, v69, vcc
	global_store_short v[4:5], v2, off
	v_mul_f32_e32 v2, v46, v86
	v_cvt_pk_bf16_f32 v2, v2, s0
	global_store_short v[4:5], v2, off offset:64
	v_mul_f32_e32 v2, v30, v86
	v_cvt_pk_bf16_f32 v2, v2, s0
	global_store_short v[4:5], v2, off offset:128
	v_mul_f32_e32 v2, v14, v86
	v_cvt_pk_bf16_f32 v2, v2, s0
	global_store_short v[4:5], v2, off offset:192
	v_mul_f32_e32 v2, v63, v87
	v_cvt_pk_bf16_f32 v2, v2, s0
	global_store_short v[4:5], v2, off offset:2048
	v_mul_f32_e32 v2, v47, v87
	v_cvt_pk_bf16_f32 v2, v2, s0
	global_store_short v[4:5], v2, off offset:2112
	v_mul_f32_e32 v2, v31, v87
	v_cvt_pk_bf16_f32 v2, v2, s0
	global_store_short v[4:5], v2, off offset:2176
	v_mul_f32_e32 v2, v15, v87
	v_cvt_pk_bf16_f32 v2, v2, s0
	global_store_short v[4:5], v2, off offset:2240
	v_mul_f32_e32 v2, v64, v72
	v_cvt_pk_bf16_f32 v2, v2, s0
	s_mov_b32 s0, 0xc000
	v_add_co_u32_e32 v4, vcc, s0, v68
	s_add_i32 s5, s5, s9
	s_nop 0
	v_addc_co_u32_e32 v5, vcc, 0, v69, vcc
	global_store_short v[4:5], v2, off
	v_mul_f32_e32 v2, v48, v72
	v_cvt_pk_bf16_f32 v2, v2, s0
	global_store_short v[4:5], v2, off offset:64
	v_mul_f32_e32 v2, v32, v72
	v_cvt_pk_bf16_f32 v2, v2, s0
	global_store_short v[4:5], v2, off offset:128
	v_mul_f32_e32 v2, v16, v72
	v_cvt_pk_bf16_f32 v2, v2, s0
	global_store_short v[4:5], v2, off offset:192
	v_mul_f32_e32 v2, v65, v73
	v_cvt_pk_bf16_f32 v2, v2, s0
	global_store_short v[4:5], v2, off offset:2048
	v_mul_f32_e32 v2, v49, v73
	v_cvt_pk_bf16_f32 v2, v2, s0
	global_store_short v[4:5], v2, off offset:2112
	v_mul_f32_e32 v2, v33, v73
	v_cvt_pk_bf16_f32 v2, v2, s0
	global_store_short v[4:5], v2, off offset:2176
	v_mul_f32_e32 v2, v17, v73
	v_cvt_pk_bf16_f32 v2, v2, s0
	global_store_short v[4:5], v2, off offset:2240
	v_mul_f32_e32 v2, v66, v74
	v_cvt_pk_bf16_f32 v2, v2, s0
	s_mov_b32 s0, 0xd000
	v_add_co_u32_e32 v4, vcc, s0, v68
	s_cmp_ge_i32 s5, s7
	s_nop 0
	v_addc_co_u32_e32 v5, vcc, 0, v69, vcc
	global_store_short v[4:5], v2, off
	v_mul_f32_e32 v2, v50, v74
	v_cvt_pk_bf16_f32 v2, v2, s0
	global_store_short v[4:5], v2, off offset:64
	v_mul_f32_e32 v2, v34, v74
	v_cvt_pk_bf16_f32 v2, v2, s0
	global_store_short v[4:5], v2, off offset:128
	v_mul_f32_e32 v2, v18, v74
	v_cvt_pk_bf16_f32 v2, v2, s0
	global_store_short v[4:5], v2, off offset:192
	v_mul_f32_e32 v2, v67, v75
	v_cvt_pk_bf16_f32 v2, v2, s0
	global_store_short v[4:5], v2, off offset:2048
	v_mul_f32_e32 v2, v51, v75
	v_cvt_pk_bf16_f32 v2, v2, s0
	global_store_short v[4:5], v2, off offset:2112
	v_mul_f32_e32 v2, v35, v75
	v_cvt_pk_bf16_f32 v2, v2, s0
	global_store_short v[4:5], v2, off offset:2176
	v_mul_f32_e32 v2, v19, v75
	v_cvt_pk_bf16_f32 v2, v2, s0
	global_store_short v[4:5], v2, off offset:2240
	s_waitcnt lgkmcnt(0)
	s_barrier
	s_cbranch_scc1 .LBB0_2438

.LBB0_2414:
	s_nop 1
	ds_read_b128 v[188:191], v181 offset:12288
	ds_read_b128 v[196:199], v181 offset:18432
	ds_read_b128 v[192:195], v182 offset:12288
	ds_read_b128 v[200:203], v182 offset:18432
	v_add_f32_e32 v2, 0, v150
	v_mov_b64_e32 v[82:83], s[30:31]
	v_add_f32_e32 v2, v151, v2
	v_mov_b64_e32 v[80:81], s[28:29]
	v_mov_b64_e32 v[78:79], s[26:27]
	v_mov_b64_e32 v[76:77], s[24:25]
	v_mov_b64_e32 v[74:75], s[22:23]
	v_mov_b64_e32 v[72:73], s[20:21]
	v_mov_b64_e32 v[70:71], s[18:19]
	v_mov_b64_e32 v[68:69], s[16:17]
	v_mov_b64_e32 v[98:99], v[82:83]
	v_add_f32_e32 v2, v152, v2
	v_mov_b64_e32 v[96:97], v[80:81]
	v_mov_b64_e32 v[94:95], v[78:79]
	v_mov_b64_e32 v[92:93], v[76:77]
	v_mov_b64_e32 v[90:91], v[74:75]
	v_mov_b64_e32 v[88:89], v[72:73]
	v_mov_b64_e32 v[86:87], v[70:71]
	v_mov_b64_e32 v[84:85], v[68:69]
	v_add_f32_e32 v2, v153, v2
	s_waitcnt lgkmcnt(1)
	v_mfma_scale_f32_32x32x64_f8f6f4 v[84:99], v[188:195], v[116:123], v[84:99], v170, v170 op_sel_hi:[0,0,0]
	s_waitcnt lgkmcnt(0)
	v_mfma_scale_f32_32x32x64_f8f6f4 v[68:83], v[196:203], v[116:123], v[68:83], v170, v170 op_sel_hi:[0,0,0]
	ds_read_b128 v[188:191], v181 offset:12352
	ds_read_b128 v[196:199], v181 offset:18496
	ds_read_b128 v[192:195], v182 offset:12352
	ds_read_b128 v[200:203], v182 offset:18496
	v_add_f32_e32 v2, v154, v2
	v_add_f32_e32 v2, v165, v2
	v_add_f32_e32 v2, v166, v2
	v_add_f32_e32 v2, v168, v2
	v_add_f32_e32 v2, v145, v2
	s_waitcnt lgkmcnt(1)
	v_mfma_scale_f32_32x32x64_f8f6f4 v[84:99], v[188:195], v[108:115], v[84:99], v170, v170 op_sel_hi:[0,0,0]
	s_waitcnt lgkmcnt(0)
	v_mfma_scale_f32_32x32x64_f8f6f4 v[68:83], v[196:203], v[108:115], v[68:83], v170, v170 op_sel_hi:[0,0,0]
	ds_read_b128 v[188:191], v181 offset:12416
	ds_read_b128 v[196:199], v181 offset:18560
	ds_read_b128 v[192:195], v182 offset:12416
	ds_read_b128 v[200:203], v182 offset:18560
	v_add_f32_e32 v2, v146, v2
	v_add_f32_e32 v2, v147, v2
	v_add_f32_e32 v2, v148, v2
	v_exp_f32_e32 v169, v140
	v_add_f32_e32 v2, v149, v2
	s_waitcnt lgkmcnt(1)
	v_mfma_scale_f32_32x32x64_f8f6f4 v[84:99], v[188:195], v[100:107], v[84:99], v170, v170 op_sel_hi:[0,0,0]
	v_exp_f32_e32 v188, v141
	v_add_f32_e32 v2, v155, v2
	v_exp_f32_e32 v136, v136
	v_add_f32_e32 v2, v164, v2
	v_exp_f32_e32 v137, v137
	v_add_f32_e32 v2, v167, v2
	v_exp_f32_e32 v134, v134
	v_add_f32_e32 v2, v169, v2
	v_exp_f32_e32 v135, v135
	v_add_f32_e32 v2, v188, v2
	v_exp_f32_e32 v130, v130
	v_add_f32_e32 v2, v136, v2
	v_exp_f32_e32 v131, v131
	v_add_f32_e32 v2, v137, v2
	v_exp_f32_e32 v128, v128
	v_add_f32_e32 v2, v134, v2
	v_exp_f32_e32 v129, v129
	v_add_f32_e32 v2, v135, v2
	v_exp_f32_e32 v189, v142
	v_add_f32_e32 v2, v130, v2
	v_exp_f32_e32 v190, v143
	v_add_f32_e32 v2, v131, v2
	v_exp_f32_e32 v138, v138
	v_add_f32_e32 v2, v128, v2
	v_exp_f32_e32 v139, v139
	v_add_f32_e32 v2, v129, v2
	v_exp_f32_e32 v132, v132
	v_add_f32_e32 v2, v189, v2
	v_exp_f32_e32 v133, v133
	v_add_f32_e32 v2, v190, v2
	v_add_f32_e32 v2, v138, v2
	v_add_f32_e32 v2, v139, v2
	v_add_f32_e32 v2, v132, v2
	v_add_f32_e32 v2, v133, v2
	v_mov_b32_e32 v187, v2
	v_cvt_pk_bf16_f32 v140, v150, v151
	v_cvt_pk_bf16_f32 v141, v152, v153
	v_cvt_pk_bf16_f32 v142, v154, v165
	v_cvt_pk_bf16_f32 v143, v166, v168
	v_cvt_pk_bf16_f32 v144, v145, v146
	v_cvt_pk_bf16_f32 v145, v147, v148
	v_cvt_pk_bf16_f32 v146, v149, v155
	v_cvt_pk_bf16_f32 v147, v164, v167
	v_cvt_pk_bf16_f32 v148, v169, v188
	v_cvt_pk_bf16_f32 v149, v136, v137
	v_cvt_pk_bf16_f32 v150, v134, v135
	v_cvt_pk_bf16_f32 v151, v130, v131
	v_cvt_pk_bf16_f32 v152, v128, v129
	v_cvt_pk_bf16_f32 v153, v189, v190
	v_cvt_pk_bf16_f32 v154, v138, v139
	v_cvt_pk_bf16_f32 v155, v132, v133
	s_waitcnt lgkmcnt(0)
	v_mfma_scale_f32_32x32x64_f8f6f4 v[68:83], v[196:203], v[100:107], v[68:83], v170, v170 op_sel_hi:[0,0,0]
	v_permlane32_swap_b32_e32 v2, v187
	v_permlane32_swap_b32_e32 v140, v142
	v_permlane32_swap_b32_e32 v141, v143
	v_permlane32_swap_b32_e32 v144, v146
	v_permlane32_swap_b32_e32 v145, v147
	v_permlane32_swap_b32_e32 v148, v150
	v_permlane32_swap_b32_e32 v149, v151
	v_permlane32_swap_b32_e32 v152, v154
	v_permlane32_swap_b32_e32 v153, v155
	s_nop 15
	s_nop 15
	v_lshl_add_u64 v[166:167], s[38:39], 0, v[162:163]
	s_mov_b32 s0, 0x2a108000
	v_add_co_u32_e32 v128, vcc, s0, v166
	v_lshl_add_u64 v[168:169], s[38:39], 0, v[160:161]
	s_nop 0
	v_addc_co_u32_e32 v129, vcc, 0, v167, vcc
	v_add_co_u32_e32 v132, vcc, 0x2a10a000, v166
	v_lshl_add_u64 v[164:165], s[38:39], 0, v[158:159]
	s_nop 0
	v_addc_co_u32_e32 v133, vcc, 0, v167, vcc
	v_add_co_u32_e32 v136, vcc, 0x1e106000, v168
	global_load_dwordx4 v[128:131], v[128:129], off
	s_nop 0
	global_load_dwordx4 v[132:135], v[132:133], off
	v_addc_co_u32_e32 v137, vcc, 0, v169, vcc
	global_load_dwordx4 v[136:139], v[136:137], off
	s_and_saveexec_b64 s[14:15], s[12:13]
	s_cbranch_execz .LBB0_2416
	v_add_co_u32_e32 v124, vcc, 0x1e106000, v164
	s_nop 1
	v_addc_co_u32_e32 v125, vcc, 0, v165, vcc
	global_load_dwordx4 v[124:127], v[124:125], off

.LBB0_2422:
	v_cndmask_b32_e64 v185, v128, v185, s[14:15]
	v_mul_f32_e32 v138, 0xbdd53b94, v185
	v_fmamk_f32 v84, v84, 0x3dd53b94, v138
	v_fmamk_f32 v85, v85, 0x3dd53b94, v138
	v_fmamk_f32 v86, v86, 0x3dd53b94, v138
	v_fmamk_f32 v87, v87, 0x3dd53b94, v138
	v_fmamk_f32 v88, v88, 0x3dd53b94, v138
	v_fmamk_f32 v89, v89, 0x3dd53b94, v138
	v_fmamk_f32 v90, v90, 0x3dd53b94, v138
	v_fmamk_f32 v91, v91, 0x3dd53b94, v138
	v_fmamk_f32 v92, v92, 0x3dd53b94, v138
	v_fmamk_f32 v93, v93, 0x3dd53b94, v138
	v_fmamk_f32 v94, v94, 0x3dd53b94, v138
	v_fmamk_f32 v95, v95, 0x3dd53b94, v138
	v_fmamk_f32 v96, v96, 0x3dd53b94, v138
	v_fmamk_f32 v97, v97, 0x3dd53b94, v138
	v_fmamk_f32 v98, v98, 0x3dd53b94, v138
	v_fmamk_f32 v99, v99, 0x3dd53b94, v138
	v_exp_f32_e32 v131, v84
	v_exp_f32_e32 v134, v85
	v_exp_f32_e32 v135, v86
	v_exp_f32_e32 v139, v87
	v_exp_f32_e32 v142, v88
	v_exp_f32_e32 v143, v89
	v_exp_f32_e32 v144, v90
	v_exp_f32_e32 v145, v91
	v_exp_f32_e32 v128, v92
	v_exp_f32_e32 v129, v93
	v_exp_f32_e32 v130, v94
	v_exp_f32_e32 v132, v95
	v_exp_f32_e32 v133, v96
	v_exp_f32_e32 v136, v97
	v_exp_f32_e32 v137, v98
	v_exp_f32_e32 v147, v99
	v_fmamk_f32 v140, v68, 0x3dd53b94, v138
	v_fmamk_f32 v141, v69, 0x3dd53b94, v138
	v_fmamk_f32 v146, v70, 0x3dd53b94, v138
	v_fmamk_f32 v148, v71, 0x3dd53b94, v138
	v_fmamk_f32 v149, v72, 0x3dd53b94, v138
	v_fmamk_f32 v150, v73, 0x3dd53b94, v138
	v_fmamk_f32 v151, v74, 0x3dd53b94, v138
	v_fmamk_f32 v152, v75, 0x3dd53b94, v138
	v_fmamk_f32 v153, v76, 0x3dd53b94, v138
	v_fmamk_f32 v154, v77, 0x3dd53b94, v138
	v_fmamk_f32 v155, v78, 0x3dd53b94, v138
	v_fmamk_f32 v189, v79, 0x3dd53b94, v138
	v_fmamk_f32 v190, v80, 0x3dd53b94, v138
	v_fmamk_f32 v191, v81, 0x3dd53b94, v138
	v_fmamk_f32 v192, v82, 0x3dd53b94, v138
	v_fmac_f32_e32 v138, 0x3dd53b94, v83
	s_waitcnt lgkmcnt(0)
	s_barrier
	s_nop 1
	ds_read_b128 v[194:197], v181
	ds_read_b128 v[202:205], v181 offset:6144
	ds_read_b128 v[198:201], v182
	ds_read_b128 v[206:209], v182 offset:6144
	v_exp_f32_e32 v193, v140
	v_add_f32_e32 v140, 0, v131
	v_mov_b64_e32 v[82:83], s[30:31]
	v_add_f32_e32 v140, v134, v140
	v_mov_b64_e32 v[80:81], s[28:29]
	v_mov_b64_e32 v[78:79], s[26:27]
	v_mov_b64_e32 v[76:77], s[24:25]
	v_mov_b64_e32 v[74:75], s[22:23]
	v_mov_b64_e32 v[72:73], s[20:21]
	v_mov_b64_e32 v[70:71], s[18:19]
	v_mov_b64_e32 v[68:69], s[16:17]
	v_mov_b64_e32 v[98:99], v[82:83]
	v_add_f32_e32 v140, v135, v140
	v_mov_b64_e32 v[96:97], v[80:81]
	v_mov_b64_e32 v[94:95], v[78:79]
	v_mov_b64_e32 v[92:93], v[76:77]
	v_mov_b64_e32 v[90:91], v[74:75]
	v_mov_b64_e32 v[88:89], v[72:73]
	v_mov_b64_e32 v[86:87], v[70:71]
	v_mov_b64_e32 v[84:85], v[68:69]
	v_add_f32_e32 v140, v139, v140
	s_waitcnt lgkmcnt(1)
	v_mfma_scale_f32_32x32x64_f8f6f4 v[84:99], v[194:201], v[116:123], v[84:99], v170, v170 op_sel_hi:[0,0,0]
	s_waitcnt lgkmcnt(0)
	v_mfma_scale_f32_32x32x64_f8f6f4 v[68:83], v[202:209], v[116:123], v[68:83], v170, v170 op_sel_hi:[0,0,0]
	ds_read_b128 v[194:197], v181 offset:64
	ds_read_b128 v[202:205], v181 offset:6208
	ds_read_b128 v[198:201], v182 offset:64
	ds_read_b128 v[206:209], v182 offset:6208
	v_add_f32_e32 v140, v142, v140
	v_add_f32_e32 v140, v143, v140
	v_add_f32_e32 v140, v144, v140
	v_add_f32_e32 v140, v145, v140
	v_add_f32_e32 v140, v128, v140
	s_waitcnt lgkmcnt(1)
	v_mfma_scale_f32_32x32x64_f8f6f4 v[84:99], v[194:201], v[108:115], v[84:99], v170, v170 op_sel_hi:[0,0,0]
	s_waitcnt lgkmcnt(0)
	v_mfma_scale_f32_32x32x64_f8f6f4 v[68:83], v[202:209], v[108:115], v[68:83], v170, v170 op_sel_hi:[0,0,0]
	ds_read_b128 v[194:197], v181 offset:128
	ds_read_b128 v[202:205], v181 offset:6272
	ds_read_b128 v[198:201], v182 offset:128
	ds_read_b128 v[206:209], v182 offset:6272
	v_add_f32_e32 v140, v129, v140
	v_add_f32_e32 v140, v130, v140
	v_add_f32_e32 v140, v132, v140
	v_add_f32_e32 v140, v133, v140
	s_waitcnt lgkmcnt(1)
	v_mfma_scale_f32_32x32x64_f8f6f4 v[84:99], v[194:201], v[100:107], v[84:99], v170, v170 op_sel_hi:[0,0,0]
	v_exp_f32_e32 v194, v141
	v_add_f32_e32 v140, v136, v140
	v_exp_f32_e32 v195, v146
	v_add_f32_e32 v140, v137, v140
	v_exp_f32_e32 v196, v148
	v_add_f32_e32 v140, v147, v140
	v_exp_f32_e32 v197, v149
	v_add_f32_e32 v140, v193, v140
	v_exp_f32_e32 v150, v150
	v_add_f32_e32 v140, v194, v140
	v_exp_f32_e32 v151, v151
	v_add_f32_e32 v140, v195, v140
	v_exp_f32_e32 v152, v152
	v_add_f32_e32 v140, v196, v140
	v_exp_f32_e32 v153, v153
	v_add_f32_e32 v140, v197, v140
	v_exp_f32_e32 v154, v154
	v_add_f32_e32 v140, v150, v140
	v_exp_f32_e32 v155, v155
	v_add_f32_e32 v140, v151, v140
	v_exp_f32_e32 v198, v189
	v_add_f32_e32 v140, v152, v140
	v_exp_f32_e32 v199, v190
	v_add_f32_e32 v140, v153, v140
	v_exp_f32_e32 v191, v191
	v_add_f32_e32 v140, v154, v140
	v_exp_f32_e32 v192, v192
	v_add_f32_e32 v140, v155, v140
	v_exp_f32_e32 v138, v138
	v_add_f32_e32 v140, v198, v140
	v_add_f32_e32 v140, v199, v140
	v_add_f32_e32 v140, v191, v140
	v_add_f32_e32 v140, v192, v140
	v_add_f32_e32 v189, v138, v140
	v_mov_b32_e32 v190, v189
	v_cvt_pk_bf16_f32 v140, v131, v134
	v_cvt_pk_bf16_f32 v141, v135, v139
	v_cvt_pk_bf16_f32 v142, v142, v143
	v_cvt_pk_bf16_f32 v143, v144, v145
	v_cvt_pk_bf16_f32 v144, v128, v129
	v_cvt_pk_bf16_f32 v145, v130, v132
	v_cvt_pk_bf16_f32 v146, v133, v136
	v_cvt_pk_bf16_f32 v147, v137, v147
	v_cvt_pk_bf16_f32 v148, v193, v194
	v_cvt_pk_bf16_f32 v149, v195, v196
	v_cvt_pk_bf16_f32 v150, v197, v150
	v_cvt_pk_bf16_f32 v151, v151, v152
	v_cvt_pk_bf16_f32 v152, v153, v154
	v_cvt_pk_bf16_f32 v153, v155, v198
	v_cvt_pk_bf16_f32 v154, v199, v191
	v_cvt_pk_bf16_f32 v155, v192, v138
	s_waitcnt lgkmcnt(0)
	v_mfma_scale_f32_32x32x64_f8f6f4 v[68:83], v[202:209], v[100:107], v[68:83], v170, v170 op_sel_hi:[0,0,0]
	v_permlane32_swap_b32_e32 v189, v190
	v_permlane32_swap_b32_e32 v140, v142
	v_permlane32_swap_b32_e32 v141, v143
	v_permlane32_swap_b32_e32 v144, v146
	v_permlane32_swap_b32_e32 v145, v147
	v_permlane32_swap_b32_e32 v148, v150
	v_permlane32_swap_b32_e32 v149, v151
	v_permlane32_swap_b32_e32 v152, v154
	v_permlane32_swap_b32_e32 v153, v155
	s_nop 15
	s_nop 15
	s_mov_b32 s0, 0x2a10c000
	v_add_co_u32_e32 v128, vcc, s0, v166
	s_nop 1
	v_addc_co_u32_e32 v129, vcc, 0, v167, vcc
	v_add_co_u32_e32 v132, vcc, 0x2a10e000, v166
	s_nop 1
	v_addc_co_u32_e32 v133, vcc, 0, v167, vcc
	v_add_co_u32_e32 v136, vcc, 0x1e109000, v168
	global_load_dwordx4 v[128:131], v[128:129], off
	s_nop 0
	global_load_dwordx4 v[132:135], v[132:133], off
	v_addc_co_u32_e32 v137, vcc, 0, v169, vcc
	global_load_dwordx4 v[136:139], v[136:137], off
	s_and_saveexec_b64 s[14:15], s[12:13]
	s_cbranch_execz .LBB0_2424
	v_add_co_u32_e32 v124, vcc, 0x1e109000, v164
	s_nop 1
	v_addc_co_u32_e32 v125, vcc, 0, v165, vcc
	global_load_dwordx4 v[124:127], v[124:125], off

.LBB0_2495:
	ds_read_b128 v[130:133], v168
	ds_read_b128 v[134:137], v168 offset:1024
	ds_read_b128 v[138:141], v168 offset:2048
	ds_read_b128 v[142:145], v168 offset:3072
	s_add_u32 s0, s36, 0xfffc0080
	s_addc_u32 s1, s37, -1
	s_cmp_eq_u32 s69, 12
	s_cselect_b32 s41, s61, s1
	s_cselect_b32 s40, s62, s0
	s_cselect_b32 s39, s63, s67
	s_cselect_b32 s38, s64, s65
	s_mov_b32 m0, s51
	v_lshl_add_u64 v[164:165], s[36:37], 0, v[162:163]
	ds_read_b128 v[146:149], v169
	ds_read_b128 v[172:175], v169 offset:1024
	ds_read_b128 v[176:179], v169 offset:2048
	ds_read_b128 v[180:183], v169 offset:3072
	ds_read_b128 v[184:187], v169 offset:4096
	ds_read_b128 v[188:191], v169 offset:5120
	ds_read_b128 v[192:195], v169 offset:6144
	ds_read_b128 v[196:199], v169 offset:7168
	global_load_lds_dwordx4 v[164:165], off
	v_lshl_add_u64 v[164:165], s[36:37], 0, v[160:161]
	s_mov_b32 m0, s52
	s_nop 0
	global_load_lds_dwordx4 v[164:165], off
	s_waitcnt lgkmcnt(8)
	s_waitcnt vmcnt(10)
	s_barrier
	s_waitcnt lgkmcnt(0)
	s_waitcnt lgkmcnt(0)
	v_mfma_f32_16x16x32_bf16 v[126:129], v[130:133], v[146:149], v[126:129]
	v_mfma_f32_16x16x32_bf16 v[122:125], v[138:141], v[146:149], v[122:125]
	v_mfma_f32_16x16x32_bf16 v[118:121], v[130:133], v[176:179], v[118:121]
	v_mfma_f32_16x16x32_bf16 v[110:113], v[138:141], v[176:179], v[110:113]
	v_mfma_f32_16x16x32_bf16 v[98:101], v[130:133], v[184:187], v[98:101]
	v_mfma_f32_16x16x32_bf16 v[90:93], v[138:141], v[184:187], v[90:93]
	v_mfma_f32_16x16x32_bf16 v[82:85], v[130:133], v[192:195], v[82:85]
	v_mfma_f32_16x16x32_bf16 v[74:77], v[138:141], v[192:195], v[74:77]
	v_mfma_f32_16x16x32_bf16 v[126:129], v[134:137], v[172:175], v[126:129]
	v_mfma_f32_16x16x32_bf16 v[122:125], v[142:145], v[172:175], v[122:125]
	v_mfma_f32_16x16x32_bf16 v[118:121], v[134:137], v[180:183], v[118:121]
	v_mfma_f32_16x16x32_bf16 v[110:113], v[142:145], v[180:183], v[110:113]
	v_mfma_f32_16x16x32_bf16 v[98:101], v[134:137], v[188:191], v[98:101]
	v_mfma_f32_16x16x32_bf16 v[90:93], v[142:145], v[188:191], v[90:93]
	v_mfma_f32_16x16x32_bf16 v[82:85], v[134:137], v[196:199], v[82:85]
	v_mfma_f32_16x16x32_bf16 v[74:77], v[142:145], v[196:199], v[74:77]
	s_barrier
	s_mov_b32 m0, s53
	v_lshl_add_u64 v[164:165], s[38:39], 0, v[156:157]
	ds_read_b128 v[200:203], v170
	ds_read_b128 v[204:207], v170 offset:1024
	ds_read_b128 v[208:211], v170 offset:2048
	ds_read_b128 v[212:215], v170 offset:3072
	global_load_lds_dwordx4 v[164:165], off
	v_lshl_add_u64 v[216:217], s[38:39], 0, v[152:153]
	s_mov_b32 m0, s54
	s_nop 0
	global_load_lds_dwordx4 v[216:217], off
	s_waitcnt vmcnt(10)
	s_barrier
	s_waitcnt lgkmcnt(0)
	s_waitcnt lgkmcnt(0)
	v_mfma_f32_16x16x32_bf16 v[114:117], v[200:203], v[146:149], v[114:117]
	v_mfma_f32_16x16x32_bf16 v[106:109], v[208:211], v[146:149], v[106:109]
	v_mfma_f32_16x16x32_bf16 v[102:105], v[200:203], v[176:179], v[102:105]
	v_mfma_f32_16x16x32_bf16 v[94:97], v[208:211], v[176:179], v[94:97]
	v_mfma_f32_16x16x32_bf16 v[86:89], v[200:203], v[184:187], v[86:89]
	v_mfma_f32_16x16x32_bf16 v[78:81], v[208:211], v[184:187], v[78:81]
	v_mfma_f32_16x16x32_bf16 v[70:73], v[200:203], v[192:195], v[70:73]
	v_mfma_f32_16x16x32_bf16 v[66:69], v[208:211], v[192:195], v[66:69]
	v_mfma_f32_16x16x32_bf16 v[114:117], v[204:207], v[172:175], v[114:117]
	v_mfma_f32_16x16x32_bf16 v[106:109], v[212:215], v[172:175], v[106:109]
	v_mfma_f32_16x16x32_bf16 v[102:105], v[204:207], v[180:183], v[102:105]
	v_mfma_f32_16x16x32_bf16 v[94:97], v[212:215], v[180:183], v[94:97]
	v_mfma_f32_16x16x32_bf16 v[86:89], v[204:207], v[188:191], v[86:89]
	v_mfma_f32_16x16x32_bf16 v[78:81], v[212:215], v[188:191], v[78:81]
	v_mfma_f32_16x16x32_bf16 v[70:73], v[204:207], v[196:199], v[70:73]
	v_mfma_f32_16x16x32_bf16 v[66:69], v[212:215], v[196:199], v[66:69]
	s_mov_b32 m0, s9
	v_lshl_add_u64 v[218:219], s[40:41], 0, v[158:159]
	s_barrier
	ds_read_b128 v[146:149], v169 offset:16384
	ds_read_b128 v[172:175], v169 offset:17408
	ds_read_b128 v[176:179], v169 offset:18432
	ds_read_b128 v[180:183], v169 offset:19456
	ds_read_b128 v[184:187], v169 offset:20480
	ds_read_b128 v[188:191], v169 offset:21504
	ds_read_b128 v[192:195], v169 offset:22528
	ds_read_b128 v[196:199], v169 offset:23552
	global_load_lds_dwordx4 v[218:219], off
	v_lshl_add_u64 v[220:221], s[40:41], 0, v[154:155]
	s_mov_b32 m0, s29
	s_nop 0
	global_load_lds_dwordx4 v[220:221], off
	s_waitcnt vmcnt(10)
	s_barrier
	s_waitcnt lgkmcnt(0)
	s_waitcnt lgkmcnt(0)
	v_mfma_f32_16x16x32_bf16 v[62:65], v[130:133], v[146:149], v[62:65]
	v_mfma_f32_16x16x32_bf16 v[58:61], v[138:141], v[146:149], v[58:61]
	v_mfma_f32_16x16x32_bf16 v[50:53], v[130:133], v[176:179], v[50:53]
	v_mfma_f32_16x16x32_bf16 v[42:45], v[138:141], v[176:179], v[42:45]
	v_mfma_f32_16x16x32_bf16 v[34:37], v[130:133], v[184:187], v[34:37]
	v_mfma_f32_16x16x32_bf16 v[26:29], v[138:141], v[184:187], v[26:29]
	v_mfma_f32_16x16x32_bf16 v[18:21], v[130:133], v[192:195], v[18:21]
	v_mfma_f32_16x16x32_bf16 v[10:13], v[138:141], v[192:195], v[10:13]
	v_mfma_f32_16x16x32_bf16 v[62:65], v[134:137], v[172:175], v[62:65]
	v_mfma_f32_16x16x32_bf16 v[58:61], v[142:145], v[172:175], v[58:61]
	v_mfma_f32_16x16x32_bf16 v[50:53], v[134:137], v[180:183], v[50:53]
	v_mfma_f32_16x16x32_bf16 v[42:45], v[142:145], v[180:183], v[42:45]
	v_mfma_f32_16x16x32_bf16 v[34:37], v[134:137], v[188:191], v[34:37]
	v_mfma_f32_16x16x32_bf16 v[26:29], v[142:145], v[188:191], v[26:29]
	v_mfma_f32_16x16x32_bf16 v[18:21], v[134:137], v[196:199], v[18:21]
	v_mfma_f32_16x16x32_bf16 v[10:13], v[142:145], v[196:199], v[10:13]
	s_barrier
	s_add_u32 s0, s38, 0x40000
	s_addc_u32 s1, s39, 0
	s_mov_b32 m0, s55
	v_lshl_add_u64 v[130:131], s[0:1], 0, v[156:157]
	global_load_lds_dwordx4 v[130:131], off
	v_lshl_add_u64 v[130:131], s[0:1], 0, v[152:153]
	s_add_i32 m0, s55, 0x2000
	s_nop 0
	global_load_lds_dwordx4 v[130:131], off
	s_waitcnt vmcnt(10)
	s_barrier
	v_mfma_f32_16x16x32_bf16 v[54:57], v[200:203], v[146:149], v[54:57]
	v_mfma_f32_16x16x32_bf16 v[46:49], v[208:211], v[146:149], v[46:49]
	v_mfma_f32_16x16x32_bf16 v[38:41], v[200:203], v[176:179], v[38:41]
	v_mfma_f32_16x16x32_bf16 v[30:33], v[208:211], v[176:179], v[30:33]
	v_mfma_f32_16x16x32_bf16 v[22:25], v[200:203], v[184:187], v[22:25]
	v_mfma_f32_16x16x32_bf16 v[14:17], v[208:211], v[184:187], v[14:17]
	v_mfma_f32_16x16x32_bf16 v[6:9], v[200:203], v[192:195], v[6:9]
	v_mfma_f32_16x16x32_bf16 v[2:5], v[208:211], v[192:195], v[2:5]
	v_mfma_f32_16x16x32_bf16 v[54:57], v[204:207], v[172:175], v[54:57]
	v_mfma_f32_16x16x32_bf16 v[46:49], v[212:215], v[172:175], v[46:49]
	v_mfma_f32_16x16x32_bf16 v[38:41], v[204:207], v[180:183], v[38:41]
	v_mfma_f32_16x16x32_bf16 v[30:33], v[212:215], v[180:183], v[30:33]
	v_mfma_f32_16x16x32_bf16 v[22:25], v[204:207], v[188:191], v[22:25]
	v_mfma_f32_16x16x32_bf16 v[14:17], v[212:215], v[188:191], v[14:17]
	v_mfma_f32_16x16x32_bf16 v[6:9], v[204:207], v[196:199], v[6:9]
	v_mfma_f32_16x16x32_bf16 v[2:5], v[212:215], v[196:199], v[2:5]
	s_add_i32 s70, 0, 0x18000
	v_add_u32_e32 v142, s70, v167
	s_barrier
	ds_read_b128 v[130:133], v142
	ds_read_b128 v[134:137], v142 offset:1024
	ds_read_b128 v[138:141], v142 offset:2048
	ds_read_b128 v[142:145], v142 offset:3072
	s_add_u32 s0, s40, 0x40000
	s_addc_u32 s1, s41, 0
	s_mov_b32 m0, s42
	v_lshl_add_u64 v[200:201], s[0:1], 0, v[158:159]
	ds_read_b128 v[146:149], v169 offset:32768
	ds_read_b128 v[172:175], v169 offset:33792
	ds_read_b128 v[176:179], v169 offset:34816
	ds_read_b128 v[180:183], v169 offset:35840
	ds_read_b128 v[184:187], v169 offset:36864
	ds_read_b128 v[188:191], v169 offset:37888
	ds_read_b128 v[192:195], v169 offset:38912
	ds_read_b128 v[196:199], v169 offset:39936
	global_load_lds_dwordx4 v[200:201], off
	v_lshl_add_u64 v[200:201], s[0:1], 0, v[154:155]
	s_mov_b32 m0, s43
	s_nop 0
	global_load_lds_dwordx4 v[200:201], off
	s_waitcnt lgkmcnt(8)
	s_waitcnt vmcnt(10)
	s_barrier
	s_waitcnt lgkmcnt(0)
	s_waitcnt lgkmcnt(0)
	v_mfma_f32_16x16x32_bf16 v[126:129], v[130:133], v[146:149], v[126:129]
	v_mfma_f32_16x16x32_bf16 v[122:125], v[138:141], v[146:149], v[122:125]
	v_mfma_f32_16x16x32_bf16 v[118:121], v[130:133], v[176:179], v[118:121]
	v_mfma_f32_16x16x32_bf16 v[110:113], v[138:141], v[176:179], v[110:113]
	v_mfma_f32_16x16x32_bf16 v[98:101], v[130:133], v[184:187], v[98:101]
	v_mfma_f32_16x16x32_bf16 v[90:93], v[138:141], v[184:187], v[90:93]
	v_mfma_f32_16x16x32_bf16 v[82:85], v[130:133], v[192:195], v[82:85]
	v_mfma_f32_16x16x32_bf16 v[74:77], v[138:141], v[192:195], v[74:77]
	v_mfma_f32_16x16x32_bf16 v[126:129], v[134:137], v[172:175], v[126:129]
	v_mfma_f32_16x16x32_bf16 v[122:125], v[142:145], v[172:175], v[122:125]
	v_mfma_f32_16x16x32_bf16 v[118:121], v[134:137], v[180:183], v[118:121]
	v_mfma_f32_16x16x32_bf16 v[110:113], v[142:145], v[180:183], v[110:113]
	v_mfma_f32_16x16x32_bf16 v[98:101], v[134:137], v[188:191], v[98:101]
	v_mfma_f32_16x16x32_bf16 v[90:93], v[142:145], v[188:191], v[90:93]
	v_mfma_f32_16x16x32_bf16 v[82:85], v[134:137], v[196:199], v[82:85]
	v_mfma_f32_16x16x32_bf16 v[74:77], v[142:145], v[196:199], v[74:77]
	s_barrier
	s_add_i32 s40, 0, 0x1c000
	s_add_i32 s0, s70, s8
	v_add_u32_e32 v171, s40, v167
	v_lshl_add_u64 v[164:165], v[164:165], 0, s[26:27]
	s_mov_b32 m0, s0
	ds_read_b128 v[200:203], v171
	ds_read_b128 v[204:207], v171 offset:1024
	ds_read_b128 v[208:211], v171 offset:2048
	ds_read_b128 v[212:215], v171 offset:3072
	global_load_lds_dwordx4 v[164:165], off
	v_lshl_add_u64 v[164:165], v[216:217], 0, s[26:27]
	s_add_i32 m0, s0, 0x2000
	s_nop 0
	global_load_lds_dwordx4 v[164:165], off
	s_waitcnt vmcnt(10)
	s_barrier
	s_waitcnt lgkmcnt(0)
	s_waitcnt lgkmcnt(0)
	v_mfma_f32_16x16x32_bf16 v[114:117], v[200:203], v[146:149], v[114:117]
	v_mfma_f32_16x16x32_bf16 v[106:109], v[208:211], v[146:149], v[106:109]
	v_mfma_f32_16x16x32_bf16 v[102:105], v[200:203], v[176:179], v[102:105]
	v_mfma_f32_16x16x32_bf16 v[94:97], v[208:211], v[176:179], v[94:97]
	v_mfma_f32_16x16x32_bf16 v[86:89], v[200:203], v[184:187], v[86:89]
	v_mfma_f32_16x16x32_bf16 v[78:81], v[208:211], v[184:187], v[78:81]
	v_mfma_f32_16x16x32_bf16 v[70:73], v[200:203], v[192:195], v[70:73]
	v_mfma_f32_16x16x32_bf16 v[66:69], v[208:211], v[192:195], v[66:69]
	v_mfma_f32_16x16x32_bf16 v[114:117], v[204:207], v[172:175], v[114:117]
	v_mfma_f32_16x16x32_bf16 v[106:109], v[212:215], v[172:175], v[106:109]
	v_mfma_f32_16x16x32_bf16 v[102:105], v[204:207], v[180:183], v[102:105]
	v_mfma_f32_16x16x32_bf16 v[94:97], v[212:215], v[180:183], v[94:97]
	v_mfma_f32_16x16x32_bf16 v[86:89], v[204:207], v[188:191], v[86:89]
	v_mfma_f32_16x16x32_bf16 v[78:81], v[212:215], v[188:191], v[78:81]
	v_mfma_f32_16x16x32_bf16 v[70:73], v[204:207], v[196:199], v[70:73]
	v_mfma_f32_16x16x32_bf16 v[66:69], v[212:215], v[196:199], v[66:69]
	s_mov_b32 m0, s49
	v_lshl_add_u64 v[164:165], v[218:219], 0, s[26:27]
	s_barrier
	ds_read_b128 v[146:149], v169 offset:49152
	ds_read_b128 v[172:175], v169 offset:50176
	ds_read_b128 v[176:179], v169 offset:51200
	ds_read_b128 v[180:183], v169 offset:52224
	ds_read_b128 v[184:187], v169 offset:53248
	ds_read_b128 v[188:191], v169 offset:54272
	ds_read_b128 v[192:195], v169 offset:55296
	ds_read_b128 v[196:199], v169 offset:56320
	global_load_lds_dwordx4 v[164:165], off
	v_lshl_add_u64 v[164:165], v[220:221], 0, s[26:27]
	s_mov_b32 m0, s50
	s_nop 0
	global_load_lds_dwordx4 v[164:165], off
	s_waitcnt vmcnt(10)
	s_barrier
	s_waitcnt lgkmcnt(0)
	s_waitcnt lgkmcnt(0)
	v_mfma_f32_16x16x32_bf16 v[62:65], v[130:133], v[146:149], v[62:65]
	v_mfma_f32_16x16x32_bf16 v[58:61], v[138:141], v[146:149], v[58:61]
	v_mfma_f32_16x16x32_bf16 v[50:53], v[130:133], v[176:179], v[50:53]
	v_mfma_f32_16x16x32_bf16 v[42:45], v[138:141], v[176:179], v[42:45]
	v_mfma_f32_16x16x32_bf16 v[34:37], v[130:133], v[184:187], v[34:37]
	v_mfma_f32_16x16x32_bf16 v[26:29], v[138:141], v[184:187], v[26:29]
	v_mfma_f32_16x16x32_bf16 v[18:21], v[130:133], v[192:195], v[18:21]
	v_mfma_f32_16x16x32_bf16 v[10:13], v[138:141], v[192:195], v[10:13]
	v_mfma_f32_16x16x32_bf16 v[62:65], v[134:137], v[172:175], v[62:65]
	v_mfma_f32_16x16x32_bf16 v[58:61], v[142:145], v[172:175], v[58:61]
	v_mfma_f32_16x16x32_bf16 v[50:53], v[134:137], v[180:183], v[50:53]
	v_mfma_f32_16x16x32_bf16 v[42:45], v[142:145], v[180:183], v[42:45]
	v_mfma_f32_16x16x32_bf16 v[34:37], v[134:137], v[188:191], v[34:37]
	v_mfma_f32_16x16x32_bf16 v[26:29], v[142:145], v[188:191], v[26:29]
	v_mfma_f32_16x16x32_bf16 v[18:21], v[134:137], v[196:199], v[18:21]
	v_mfma_f32_16x16x32_bf16 v[10:13], v[142:145], v[196:199], v[10:13]
	s_barrier
	s_add_u32 s0, s38, 0x40080
	s_addc_u32 s1, s39, 0
	s_add_i32 s38, s40, s8
	v_lshl_add_u64 v[130:131], s[0:1], 0, v[156:157]
	s_mov_b32 m0, s38
	s_nop 0
	global_load_lds_dwordx4 v[130:131], off
	v_lshl_add_u64 v[130:131], s[0:1], 0, v[152:153]
	s_add_i32 m0, s38, 0x2000
	s_nop 0
	global_load_lds_dwordx4 v[130:131], off
	s_waitcnt vmcnt(10)
	s_barrier
	v_mfma_f32_16x16x32_bf16 v[54:57], v[200:203], v[146:149], v[54:57]
	v_mfma_f32_16x16x32_bf16 v[46:49], v[208:211], v[146:149], v[46:49]
	v_mfma_f32_16x16x32_bf16 v[38:41], v[200:203], v[176:179], v[38:41]
	v_mfma_f32_16x16x32_bf16 v[30:33], v[208:211], v[176:179], v[30:33]
	v_mfma_f32_16x16x32_bf16 v[22:25], v[200:203], v[184:187], v[22:25]
	v_mfma_f32_16x16x32_bf16 v[14:17], v[208:211], v[184:187], v[14:17]
	v_mfma_f32_16x16x32_bf16 v[6:9], v[200:203], v[192:195], v[6:9]
	v_mfma_f32_16x16x32_bf16 v[2:5], v[208:211], v[192:195], v[2:5]
	v_mfma_f32_16x16x32_bf16 v[54:57], v[204:207], v[172:175], v[54:57]
	v_mfma_f32_16x16x32_bf16 v[46:49], v[212:215], v[172:175], v[46:49]
	v_mfma_f32_16x16x32_bf16 v[38:41], v[204:207], v[180:183], v[38:41]
	v_mfma_f32_16x16x32_bf16 v[30:33], v[212:215], v[180:183], v[30:33]
	v_mfma_f32_16x16x32_bf16 v[22:25], v[204:207], v[188:191], v[22:25]
	v_mfma_f32_16x16x32_bf16 v[14:17], v[212:215], v[188:191], v[14:17]
	v_mfma_f32_16x16x32_bf16 v[6:9], v[204:207], v[196:199], v[6:9]
	v_mfma_f32_16x16x32_bf16 v[2:5], v[212:215], v[196:199], v[2:5]
	s_add_i32 s69, s69, 2
	s_add_u32 s65, s65, 0x100
	s_addc_u32 s67, s67, 0
	s_add_u32 s36, s36, 0x100
	s_addc_u32 s37, s37, 0
	s_cmp_gt_u32 s69, 13
	s_barrier
	s_cbranch_scc0 .LBB0_2495
	s_lshl_b32 s0, s59, 8
	v_mov_b32_e32 v130, v151
	v_mov_b32_e32 v131, v166
	s_or_b32 s0, s0, s46
	s_mov_b32 s59, s58
	v_lshl_add_u32 v164, v131, 3, s0
	s_lshl_b32 s0, s60, 8
	s_add_i32 s0, s0, s45
	v_add_u32_e32 v171, s0, v130
	v_mov_b32_e32 v130, v171
	v_ashrrev_i32_e32 v165, 31, v164
	v_ashrrev_i32_e32 v131, 31, v130
	v_lshlrev_b64 v[130:131], 10, v[130:131]
	v_lshl_add_u64 v[130:131], v[130:131], 0, v[164:165]
	v_lshlrev_b64 v[184:185], 1, v[130:131]
	v_lshl_add_u64 v[130:131], s[10:11], 0, v[184:185]
	global_load_dwordx4 v[172:175], v[130:131], off
	global_load_dwordx4 v[176:179], v[130:131], off offset:256
	v_add_co_u32_e32 v132, vcc, s48, v130
	s_mov_b32 s60, s57
	s_nop 0
	v_addc_co_u32_e32 v133, vcc, 0, v131, vcc
	global_load_dwordx4 v[180:183], v[132:133], off
	global_load_dwordx4 v[146:149], v[132:133], off offset:256
	v_add_co_u32_e32 v132, vcc, s44, v130
	s_waitcnt vmcnt(0) lgkmcnt(0)
	v_lshlrev_b32_e32 v186, 16, v172
	v_addc_co_u32_e32 v133, vcc, 0, v131, vcc
	global_load_dwordx4 v[142:145], v[132:133], off
	global_load_dwordx4 v[138:141], v[132:133], off offset:256
	v_add_co_u32_e32 v130, vcc, s47, v130
	v_and_b32_e32 v187, 0xffff0000, v172
	s_nop 0
	v_addc_co_u32_e32 v131, vcc, 0, v131, vcc
	global_load_dwordx4 v[134:137], v[130:131], off
	s_nop 0
	global_load_dwordx4 v[130:133], v[130:131], off offset:256
	v_lshlrev_b32_e32 v172, 16, v173
	v_and_b32_e32 v173, 0xffff0000, v173
	v_lshlrev_b32_e32 v188, 16, v174
	v_and_b32_e32 v189, 0xffff0000, v174
	v_lshlrev_b32_e32 v174, 16, v175
	v_and_b32_e32 v175, 0xffff0000, v175
	v_pk_fma_f32 v[128:129], v[172:173], s[28:29], v[128:129] op_sel_hi:[1,0,1]
	v_pk_fma_f32 v[126:127], v[186:187], s[28:29], v[126:127] op_sel_hi:[1,0,1]
	v_pk_fma_f32 v[172:173], v[174:175], s[28:29], v[124:125] op_sel_hi:[1,0,1]
	v_pk_fma_f32 v[122:123], v[188:189], s[28:29], v[122:123] op_sel_hi:[1,0,1]
	v_cvt_pk_bf16_f32 v124, v126, v127
	v_cvt_pk_bf16_f32 v125, v128, v129
	v_cvt_pk_bf16_f32 v126, v122, v123
	v_cvt_pk_bf16_f32 v127, v172, v173
	v_lshl_add_u64 v[122:123], s[16:17], 0, v[184:185]
	global_store_dwordx4 v[122:123], v[124:127], off
	v_lshlrev_b32_e32 v128, 16, v178
	v_and_b32_e32 v129, 0xffff0000, v178
	v_lshlrev_b32_e32 v124, 16, v176
	v_and_b32_e32 v125, 0xffff0000, v176
	v_lshlrev_b32_e32 v126, 16, v177
	v_and_b32_e32 v127, 0xffff0000, v177
	v_lshlrev_b32_e32 v172, 16, v179
	v_and_b32_e32 v173, 0xffff0000, v179
	v_pk_fma_f32 v[116:117], v[126:127], s[28:29], v[116:117] op_sel_hi:[1,0,1]
	v_pk_fma_f32 v[114:115], v[124:125], s[28:29], v[114:115] op_sel_hi:[1,0,1]
	v_pk_fma_f32 v[124:125], v[172:173], s[28:29], v[108:109] op_sel_hi:[1,0,1]
	v_pk_fma_f32 v[108:109], v[128:129], s[28:29], v[106:107] op_sel_hi:[1,0,1]
	v_cvt_pk_bf16_f32 v106, v114, v115
	v_cvt_pk_bf16_f32 v107, v116, v117
	v_cvt_pk_bf16_f32 v108, v108, v109
	v_cvt_pk_bf16_f32 v109, v124, v125
	global_store_dwordx4 v[122:123], v[106:109], off offset:256
	v_lshlrev_b32_e32 v114, 16, v182
	v_and_b32_e32 v115, 0xffff0000, v182
	v_lshlrev_b32_e32 v106, 16, v180
	v_and_b32_e32 v107, 0xffff0000, v180
	v_lshlrev_b32_e32 v108, 16, v181
	v_and_b32_e32 v109, 0xffff0000, v181
	v_lshlrev_b32_e32 v116, 16, v183
	v_and_b32_e32 v117, 0xffff0000, v183
	v_pk_fma_f32 v[108:109], v[108:109], s[28:29], v[120:121] op_sel_hi:[1,0,1]
	v_pk_fma_f32 v[106:107], v[106:107], s[28:29], v[118:119] op_sel_hi:[1,0,1]
	v_pk_fma_f32 v[110:111], v[114:115], s[28:29], v[110:111] op_sel_hi:[1,0,1]
	v_pk_fma_f32 v[112:113], v[116:117], s[28:29], v[112:113] op_sel_hi:[1,0,1]
	v_cvt_pk_bf16_f32 v106, v106, v107
	v_cvt_pk_bf16_f32 v107, v108, v109
	v_cvt_pk_bf16_f32 v108, v110, v111
	v_add_co_u32_e32 v110, vcc, s48, v122
	v_cvt_pk_bf16_f32 v109, v112, v113
	s_nop 0
	v_addc_co_u32_e32 v111, vcc, 0, v123, vcc
	global_store_dwordx4 v[110:111], v[106:109], off
	v_lshlrev_b32_e32 v112, 16, v148
	v_and_b32_e32 v113, 0xffff0000, v148
	v_lshlrev_b32_e32 v106, 16, v146
	v_and_b32_e32 v107, 0xffff0000, v146
	v_lshlrev_b32_e32 v108, 16, v147
	v_and_b32_e32 v109, 0xffff0000, v147
	v_lshlrev_b32_e32 v114, 16, v149
	v_and_b32_e32 v115, 0xffff0000, v149
	v_pk_fma_f32 v[104:105], v[108:109], s[28:29], v[104:105] op_sel_hi:[1,0,1]
	v_pk_fma_f32 v[102:103], v[106:107], s[28:29], v[102:103] op_sel_hi:[1,0,1]
	v_pk_fma_f32 v[106:107], v[114:115], s[28:29], v[96:97] op_sel_hi:[1,0,1]
	v_pk_fma_f32 v[96:97], v[112:113], s[28:29], v[94:95] op_sel_hi:[1,0,1]
	v_cvt_pk_bf16_f32 v94, v102, v103
	v_cvt_pk_bf16_f32 v95, v104, v105
	v_cvt_pk_bf16_f32 v96, v96, v97
	v_cvt_pk_bf16_f32 v97, v106, v107
	global_store_dwordx4 v[110:111], v[94:97], off offset:256
	s_waitcnt vmcnt(0) lgkmcnt(0)
	v_lshlrev_b32_e32 v102, 16, v144
	v_lshlrev_b32_e32 v94, 16, v142
	v_and_b32_e32 v95, 0xffff0000, v142
	v_lshlrev_b32_e32 v96, 16, v143
	v_and_b32_e32 v97, 0xffff0000, v143
	v_and_b32_e32 v103, 0xffff0000, v144
	v_lshlrev_b32_e32 v104, 16, v145
	v_and_b32_e32 v105, 0xffff0000, v145
	v_pk_fma_f32 v[94:95], v[94:95], s[28:29], v[98:99] op_sel_hi:[1,0,1]
	v_pk_fma_f32 v[96:97], v[96:97], s[28:29], v[100:101] op_sel_hi:[1,0,1]
	v_pk_fma_f32 v[98:99], v[104:105], s[28:29], v[92:93] op_sel_hi:[1,0,1]
	v_pk_fma_f32 v[92:93], v[102:103], s[28:29], v[90:91] op_sel_hi:[1,0,1]
	v_cvt_pk_bf16_f32 v90, v94, v95
	v_add_co_u32_e32 v94, vcc, s44, v122
	v_cvt_pk_bf16_f32 v91, v96, v97
	v_cvt_pk_bf16_f32 v92, v92, v93
	v_cvt_pk_bf16_f32 v93, v98, v99
	v_addc_co_u32_e32 v95, vcc, 0, v123, vcc
	global_store_dwordx4 v[94:95], v[90:93], off
	v_lshlrev_b32_e32 v96, 16, v140
	v_and_b32_e32 v97, 0xffff0000, v140
	v_lshlrev_b32_e32 v90, 16, v138
	v_and_b32_e32 v91, 0xffff0000, v138
	v_lshlrev_b32_e32 v92, 16, v139
	v_and_b32_e32 v93, 0xffff0000, v139
	v_lshlrev_b32_e32 v98, 16, v141
	v_and_b32_e32 v99, 0xffff0000, v141
	v_pk_fma_f32 v[88:89], v[92:93], s[28:29], v[88:89] op_sel_hi:[1,0,1]
	v_pk_fma_f32 v[86:87], v[90:91], s[28:29], v[86:87] op_sel_hi:[1,0,1]
	v_pk_fma_f32 v[90:91], v[98:99], s[28:29], v[80:81] op_sel_hi:[1,0,1]
	v_pk_fma_f32 v[80:81], v[96:97], s[28:29], v[78:79] op_sel_hi:[1,0,1]
	v_cvt_pk_bf16_f32 v78, v86, v87
	v_cvt_pk_bf16_f32 v79, v88, v89
	v_cvt_pk_bf16_f32 v80, v80, v81
	v_cvt_pk_bf16_f32 v81, v90, v91
	global_store_dwordx4 v[94:95], v[78:81], off offset:256
	v_lshlrev_b32_e32 v86, 16, v136
	v_and_b32_e32 v87, 0xffff0000, v136
	v_lshlrev_b32_e32 v78, 16, v134
	v_and_b32_e32 v79, 0xffff0000, v134
	v_lshlrev_b32_e32 v80, 16, v135
	v_and_b32_e32 v81, 0xffff0000, v135
	v_lshlrev_b32_e32 v88, 16, v137
	v_and_b32_e32 v89, 0xffff0000, v137
	v_pk_fma_f32 v[78:79], v[78:79], s[28:29], v[82:83] op_sel_hi:[1,0,1]
	v_pk_fma_f32 v[80:81], v[80:81], s[28:29], v[84:85] op_sel_hi:[1,0,1]
	v_pk_fma_f32 v[82:83], v[88:89], s[28:29], v[76:77] op_sel_hi:[1,0,1]
	v_pk_fma_f32 v[76:77], v[86:87], s[28:29], v[74:75] op_sel_hi:[1,0,1]
	v_cvt_pk_bf16_f32 v74, v78, v79
	v_add_co_u32_e32 v78, vcc, s47, v122
	v_cvt_pk_bf16_f32 v75, v80, v81
	v_cvt_pk_bf16_f32 v76, v76, v77
	v_cvt_pk_bf16_f32 v77, v82, v83
	v_addc_co_u32_e32 v79, vcc, 0, v123, vcc
	global_store_dwordx4 v[78:79], v[74:77], off
	v_lshlrev_b32_e32 v80, 16, v132
	v_and_b32_e32 v81, 0xffff0000, v132
	v_lshlrev_b32_e32 v74, 16, v130
	v_and_b32_e32 v75, 0xffff0000, v130
	v_lshlrev_b32_e32 v76, 16, v131
	v_and_b32_e32 v77, 0xffff0000, v131
	v_lshlrev_b32_e32 v82, 16, v133
	v_and_b32_e32 v83, 0xffff0000, v133
	v_pk_fma_f32 v[72:73], v[76:77], s[28:29], v[72:73] op_sel_hi:[1,0,1]
	v_pk_fma_f32 v[70:71], v[74:75], s[28:29], v[70:71] op_sel_hi:[1,0,1]
	v_pk_fma_f32 v[74:75], v[82:83], s[28:29], v[68:69] op_sel_hi:[1,0,1]
	v_pk_fma_f32 v[68:69], v[80:81], s[28:29], v[66:67] op_sel_hi:[1,0,1]
	v_cvt_pk_bf16_f32 v66, v70, v71
	v_cvt_pk_bf16_f32 v67, v72, v73
	v_cvt_pk_bf16_f32 v68, v68, v69
	v_cvt_pk_bf16_f32 v69, v74, v75
	global_store_dwordx4 v[78:79], v[66:69], off offset:256
	s_nop 1
	v_add_u32_e32 v66, 0x80, v171
	s_nop 0
	v_ashrrev_i32_e32 v67, 31, v66
	v_lshlrev_b64 v[66:67], 10, v[66:67]
	v_lshl_add_u64 v[66:67], v[66:67], 0, v[164:165]
	v_lshlrev_b64 v[98:99], 1, v[66:67]
	v_lshl_add_u64 v[90:91], s[10:11], 0, v[98:99]
	global_load_dwordx4 v[66:69], v[90:91], off
	global_load_dwordx4 v[70:73], v[90:91], off offset:256
	v_add_co_u32_e32 v78, vcc, s48, v90
	s_waitcnt vmcnt(0) lgkmcnt(0)
	v_lshlrev_b32_e32 v100, 16, v66
	v_addc_co_u32_e32 v79, vcc, 0, v91, vcc
	global_load_dwordx4 v[74:77], v[78:79], off
	s_nop 0
	global_load_dwordx4 v[78:81], v[78:79], off offset:256
	v_add_co_u32_e32 v86, vcc, s44, v90
	v_and_b32_e32 v101, 0xffff0000, v66
	s_nop 0
	v_addc_co_u32_e32 v87, vcc, 0, v91, vcc
	global_load_dwordx4 v[82:85], v[86:87], off
	s_nop 0
	global_load_dwordx4 v[86:89], v[86:87], off offset:256
	v_add_co_u32_e32 v94, vcc, s47, v90
	v_lshlrev_b32_e32 v66, 16, v67
	s_nop 0
	v_addc_co_u32_e32 v95, vcc, 0, v91, vcc
	global_load_dwordx4 v[90:93], v[94:95], off
	s_nop 0
	global_load_dwordx4 v[94:97], v[94:95], off offset:256
	v_and_b32_e32 v67, 0xffff0000, v67
	v_lshlrev_b32_e32 v102, 16, v68
	v_and_b32_e32 v103, 0xffff0000, v68
	v_lshlrev_b32_e32 v68, 16, v69
	v_and_b32_e32 v69, 0xffff0000, v69
	v_pk_fma_f32 v[64:65], v[66:67], s[28:29], v[64:65] op_sel_hi:[1,0,1]
	v_pk_fma_f32 v[62:63], v[100:101], s[28:29], v[62:63] op_sel_hi:[1,0,1]
	v_pk_fma_f32 v[66:67], v[68:69], s[28:29], v[60:61] op_sel_hi:[1,0,1]
	v_pk_fma_f32 v[60:61], v[102:103], s[28:29], v[58:59] op_sel_hi:[1,0,1]
	v_cvt_pk_bf16_f32 v58, v62, v63
	v_cvt_pk_bf16_f32 v59, v64, v65
	v_cvt_pk_bf16_f32 v60, v60, v61
	v_cvt_pk_bf16_f32 v61, v66, v67
	v_lshl_add_u64 v[62:63], s[16:17], 0, v[98:99]
	global_store_dwordx4 v[62:63], v[58:61], off
	v_lshlrev_b32_e32 v64, 16, v72
	v_and_b32_e32 v65, 0xffff0000, v72
	v_lshlrev_b32_e32 v58, 16, v70
	v_and_b32_e32 v59, 0xffff0000, v70
	v_lshlrev_b32_e32 v60, 16, v71
	v_and_b32_e32 v61, 0xffff0000, v71
	v_lshlrev_b32_e32 v66, 16, v73
	v_and_b32_e32 v67, 0xffff0000, v73
	v_pk_fma_f32 v[56:57], v[60:61], s[28:29], v[56:57] op_sel_hi:[1,0,1]
	v_pk_fma_f32 v[54:55], v[58:59], s[28:29], v[54:55] op_sel_hi:[1,0,1]
	v_pk_fma_f32 v[58:59], v[66:67], s[28:29], v[48:49] op_sel_hi:[1,0,1]
	v_pk_fma_f32 v[48:49], v[64:65], s[28:29], v[46:47] op_sel_hi:[1,0,1]
	v_cvt_pk_bf16_f32 v46, v54, v55
	v_cvt_pk_bf16_f32 v47, v56, v57
	v_cvt_pk_bf16_f32 v48, v48, v49
	v_cvt_pk_bf16_f32 v49, v58, v59
	global_store_dwordx4 v[62:63], v[46:49], off offset:256
	s_waitcnt vmcnt(0) lgkmcnt(0)
	v_lshlrev_b32_e32 v54, 16, v76
	v_lshlrev_b32_e32 v46, 16, v74
	v_and_b32_e32 v47, 0xffff0000, v74
	v_lshlrev_b32_e32 v48, 16, v75
	v_and_b32_e32 v49, 0xffff0000, v75
	v_and_b32_e32 v55, 0xffff0000, v76
	v_lshlrev_b32_e32 v56, 16, v77
	v_and_b32_e32 v57, 0xffff0000, v77
	v_pk_fma_f32 v[46:47], v[46:47], s[28:29], v[50:51] op_sel_hi:[1,0,1]
	v_pk_fma_f32 v[48:49], v[48:49], s[28:29], v[52:53] op_sel_hi:[1,0,1]
	v_pk_fma_f32 v[50:51], v[56:57], s[28:29], v[44:45] op_sel_hi:[1,0,1]
	v_pk_fma_f32 v[44:45], v[54:55], s[28:29], v[42:43] op_sel_hi:[1,0,1]
	v_cvt_pk_bf16_f32 v42, v46, v47
	v_add_co_u32_e32 v46, vcc, s48, v62
	v_cvt_pk_bf16_f32 v43, v48, v49
	v_cvt_pk_bf16_f32 v44, v44, v45
	v_cvt_pk_bf16_f32 v45, v50, v51
	v_addc_co_u32_e32 v47, vcc, 0, v63, vcc
	global_store_dwordx4 v[46:47], v[42:45], off
	v_lshlrev_b32_e32 v48, 16, v80
	v_and_b32_e32 v49, 0xffff0000, v80
	v_lshlrev_b32_e32 v42, 16, v78
	v_and_b32_e32 v43, 0xffff0000, v78
	v_lshlrev_b32_e32 v44, 16, v79
	v_and_b32_e32 v45, 0xffff0000, v79
	v_lshlrev_b32_e32 v50, 16, v81
	v_and_b32_e32 v51, 0xffff0000, v81
	v_pk_fma_f32 v[40:41], v[44:45], s[28:29], v[40:41] op_sel_hi:[1,0,1]
	v_pk_fma_f32 v[38:39], v[42:43], s[28:29], v[38:39] op_sel_hi:[1,0,1]
	v_pk_fma_f32 v[42:43], v[50:51], s[28:29], v[32:33] op_sel_hi:[1,0,1]
	v_pk_fma_f32 v[32:33], v[48:49], s[28:29], v[30:31] op_sel_hi:[1,0,1]
	v_cvt_pk_bf16_f32 v30, v38, v39
	v_cvt_pk_bf16_f32 v31, v40, v41
	v_cvt_pk_bf16_f32 v32, v32, v33
	v_cvt_pk_bf16_f32 v33, v42, v43
	global_store_dwordx4 v[46:47], v[30:33], off offset:256
	v_lshlrev_b32_e32 v38, 16, v84
	v_and_b32_e32 v39, 0xffff0000, v84
	v_lshlrev_b32_e32 v30, 16, v82
	v_and_b32_e32 v31, 0xffff0000, v82
	v_lshlrev_b32_e32 v32, 16, v83
	v_and_b32_e32 v33, 0xffff0000, v83
	v_lshlrev_b32_e32 v40, 16, v85
	v_and_b32_e32 v41, 0xffff0000, v85
	v_pk_fma_f32 v[30:31], v[30:31], s[28:29], v[34:35] op_sel_hi:[1,0,1]
	v_pk_fma_f32 v[32:33], v[32:33], s[28:29], v[36:37] op_sel_hi:[1,0,1]
	v_pk_fma_f32 v[34:35], v[40:41], s[28:29], v[28:29] op_sel_hi:[1,0,1]
	v_pk_fma_f32 v[28:29], v[38:39], s[28:29], v[26:27] op_sel_hi:[1,0,1]
	v_cvt_pk_bf16_f32 v26, v30, v31
	v_add_co_u32_e32 v30, vcc, s44, v62
	v_cvt_pk_bf16_f32 v27, v32, v33
	v_cvt_pk_bf16_f32 v28, v28, v29
	v_cvt_pk_bf16_f32 v29, v34, v35
	v_addc_co_u32_e32 v31, vcc, 0, v63, vcc
	global_store_dwordx4 v[30:31], v[26:29], off
	v_lshlrev_b32_e32 v32, 16, v88
	v_and_b32_e32 v33, 0xffff0000, v88
	v_lshlrev_b32_e32 v26, 16, v86
	v_and_b32_e32 v27, 0xffff0000, v86
	v_lshlrev_b32_e32 v28, 16, v87
	v_and_b32_e32 v29, 0xffff0000, v87
	v_lshlrev_b32_e32 v34, 16, v89
	v_and_b32_e32 v35, 0xffff0000, v89
	v_pk_fma_f32 v[24:25], v[28:29], s[28:29], v[24:25] op_sel_hi:[1,0,1]
	v_pk_fma_f32 v[22:23], v[26:27], s[28:29], v[22:23] op_sel_hi:[1,0,1]
	v_pk_fma_f32 v[26:27], v[34:35], s[28:29], v[16:17] op_sel_hi:[1,0,1]
	v_pk_fma_f32 v[16:17], v[32:33], s[28:29], v[14:15] op_sel_hi:[1,0,1]
	v_cvt_pk_bf16_f32 v14, v22, v23
	v_cvt_pk_bf16_f32 v15, v24, v25
	v_cvt_pk_bf16_f32 v16, v16, v17
	v_cvt_pk_bf16_f32 v17, v26, v27
	global_store_dwordx4 v[30:31], v[14:17], off offset:256
	v_lshlrev_b32_e32 v22, 16, v92
	v_and_b32_e32 v23, 0xffff0000, v92
	v_lshlrev_b32_e32 v14, 16, v90
	v_and_b32_e32 v15, 0xffff0000, v90
	v_lshlrev_b32_e32 v16, 16, v91
	v_and_b32_e32 v17, 0xffff0000, v91
	v_lshlrev_b32_e32 v24, 16, v93
	v_and_b32_e32 v25, 0xffff0000, v93
	v_pk_fma_f32 v[14:15], v[14:15], s[28:29], v[18:19] op_sel_hi:[1,0,1]
	v_pk_fma_f32 v[16:17], v[16:17], s[28:29], v[20:21] op_sel_hi:[1,0,1]
	v_pk_fma_f32 v[18:19], v[24:25], s[28:29], v[12:13] op_sel_hi:[1,0,1]
	v_pk_fma_f32 v[12:13], v[22:23], s[28:29], v[10:11] op_sel_hi:[1,0,1]
	v_cvt_pk_bf16_f32 v10, v14, v15
	v_add_co_u32_e32 v14, vcc, s47, v62
	v_cvt_pk_bf16_f32 v11, v16, v17
	v_cvt_pk_bf16_f32 v12, v12, v13
	v_cvt_pk_bf16_f32 v13, v18, v19
	v_addc_co_u32_e32 v15, vcc, 0, v63, vcc
	global_store_dwordx4 v[14:15], v[10:13], off
	v_lshlrev_b32_e32 v16, 16, v96
	v_and_b32_e32 v17, 0xffff0000, v96
	v_lshlrev_b32_e32 v10, 16, v94
	v_and_b32_e32 v11, 0xffff0000, v94
	v_lshlrev_b32_e32 v12, 16, v95
	v_and_b32_e32 v13, 0xffff0000, v95
	v_lshlrev_b32_e32 v18, 16, v97
	v_and_b32_e32 v19, 0xffff0000, v97
	v_pk_fma_f32 v[8:9], v[12:13], s[28:29], v[8:9] op_sel_hi:[1,0,1]
	v_pk_fma_f32 v[6:7], v[10:11], s[28:29], v[6:7] op_sel_hi:[1,0,1]
	v_pk_fma_f32 v[10:11], v[18:19], s[28:29], v[4:5] op_sel_hi:[1,0,1]
	v_pk_fma_f32 v[4:5], v[16:17], s[28:29], v[2:3] op_sel_hi:[1,0,1]
	v_cvt_pk_bf16_f32 v2, v6, v7
	v_cvt_pk_bf16_f32 v3, v8, v9
	v_cvt_pk_bf16_f32 v4, v4, v5
	v_cvt_pk_bf16_f32 v5, v10, v11
	s_and_b64 vcc, exec, s[30:31]
	global_store_dwordx4 v[14:15], v[2:5], off offset:256
	s_cbranch_vccz .LBB0_2494
	s_waitcnt vmcnt(0)
	s_cmpk_gt_u32 s5, 0xff
	s_cbranch_scc1 .LBB0_2499
	s_barrier

.LBB0_2516:
	s_or_b64 exec, exec, s[18:19]
	s_lshl_b32 s0, s9, 8
	s_add_i32 s0, s0, s97
	s_ashr_i32 s1, s0, 31
	s_lshl_b64 s[18:19], s[0:1], 11
	v_lshl_add_u64 v[38:39], v[54:55], 0, s[18:19]
	s_mov_b64 s[18:19], 0x4000
	v_add_co_u32_e32 v44, vcc, 0x4000, v38
	s_waitcnt lgkmcnt(0)
	s_barrier
	global_load_dwordx4 v[2:5], v[50:51], off
	global_load_dwordx4 v[6:9], v[50:51], off offset:1024
	global_load_dwordx4 v[10:13], v[52:53], off
	global_load_dwordx4 v[14:17], v[52:53], off offset:1024
	global_load_dwordx4 v[18:21], v[50:51], off offset:2048
	global_load_dwordx4 v[22:25], v[50:51], off offset:3072
	global_load_dwordx4 v[26:29], v[52:53], off offset:2048
	global_load_dwordx4 v[30:33], v[52:53], off offset:3072
	v_lshl_add_u64 v[42:43], v[38:39], 0, s[18:19]
	v_addc_co_u32_e32 v45, vcc, 0, v39, vcc
	global_load_dwordx2 v[36:37], v[38:39], off
	global_load_dwordx2 v[34:35], v[38:39], off offset:512
	global_load_dwordx2 v[40:41], v[38:39], off offset:1024
	s_nop 0
	global_load_dwordx2 v[38:39], v[38:39], off offset:1536
	s_nop 0
	global_load_dwordx2 v[60:61], v[44:45], off
	global_load_dwordx2 v[62:63], v[42:43], off offset:512
	global_load_dwordx2 v[64:65], v[42:43], off offset:1024
	global_load_dwordx2 v[66:67], v[42:43], off offset:1536
	s_mov_b32 s28, 0
	s_add_i32 s29, s0, 16
	s_mov_b32 s30, 0
	s_branch .LBB0_2519

.LBB0_2519:
	s_waitcnt vmcnt(0) lgkmcnt(0)
	v_lshlrev_b32_e32 v77, 16, v37
	v_lshlrev_b32_e32 v76, 16, v36
	v_and_b32_e32 v37, 0xffff0000, v37
	v_and_b32_e32 v36, 0xffff0000, v36
	v_pk_add_f32 v[68:69], v[76:77], v[36:37]
	v_lshlrev_b32_e32 v87, 16, v35
	v_lshlrev_b32_e32 v86, 16, v34
	v_and_b32_e32 v35, 0xffff0000, v35
	v_and_b32_e32 v34, 0xffff0000, v34
	v_lshlrev_b32_e32 v46, 16, v39
	v_and_b32_e32 v48, 0xffff0000, v39
	v_add_f32_e32 v39, v68, v69
	v_pk_add_f32 v[68:69], v[86:87], v[34:35]
	v_lshlrev_b32_e32 v42, 16, v40
	v_and_b32_e32 v43, 0xffff0000, v40
	v_lshlrev_b32_e32 v40, 16, v41
	v_and_b32_e32 v41, 0xffff0000, v41
	v_pk_add_f32 v[68:69], v[68:69], v[68:69] op_sel_hi:[0,1]
	v_lshlrev_b32_e32 v44, 16, v38
	v_and_b32_e32 v38, 0xffff0000, v38
	v_add_f32_e32 v49, 0, v39
	v_add_f32_e32 v45, v42, v43
	v_add_f32_e32 v39, v40, v41
	v_mov_b32_e32 v47, v69
	v_pk_add_f32 v[70:71], v[44:45], v[38:39]
	v_pk_add_f32 v[68:69], v[46:47], v[48:49]
	s_min_u32 s0, s30, 29
	v_pk_add_f32 v[68:69], v[70:71], v[68:69]
	s_lshl_b32 s0, s0, 3
	v_add_f32_e32 v39, v68, v69
	s_add_i32 s18, s29, s0
	s_nop 0
	v_add_f32_dpp v39, v39, v39 quad_perm:[1,0,3,2] row_mask:0xf bank_mask:0xf bound_ctrl:1
	s_nop 1
	v_add_f32_dpp v39, v39, v39 quad_perm:[2,3,0,1] row_mask:0xf bank_mask:0xf bound_ctrl:1
	s_nop 1
	v_add_f32_dpp v39, v39, v39 row_half_mirror row_mask:0xf bank_mask:0xf bound_ctrl:1
	s_nop 1
	v_add_f32_dpp v39, v39, v39 row_mirror row_mask:0xf bank_mask:0xf bound_ctrl:1
	s_nop 0
	v_readlane_b32 s19, v39, 16
	v_readlane_b32 s22, v39, 48
	v_readlane_b32 s0, v39, 0
	v_readlane_b32 s1, v39, 32
	v_mov_b32_e32 v68, s19
	v_mov_b32_e32 v69, s22
	v_pk_add_f32 v[68:69], s[0:1], v[68:69]
	s_nop 0
	v_add_f32_e32 v39, v68, v69
	v_fmac_f32_e32 v36, 0xba800000, v39
	v_fmac_f32_e32 v37, 0xba800000, v39
	v_fmac_f32_e32 v77, 0xba800000, v39
	v_fmac_f32_e32 v76, 0xba800000, v39
	v_mov_b32_e32 v88, v77
	v_mov_b32_e32 v89, v37
	v_mov_b32_e32 v77, v36
	v_fmac_f32_e32 v34, 0xba800000, v39
	v_fmac_f32_e32 v35, 0xba800000, v39
	v_fmac_f32_e32 v87, 0xba800000, v39
	v_pk_mul_f32 v[68:69], v[88:89], v[88:89]
	v_pk_mul_f32 v[36:37], v[76:77], v[76:77]
	v_fmac_f32_e32 v86, 0xba800000, v39
	v_mov_b32_e32 v90, v87
	v_mov_b32_e32 v91, v35
	v_mov_b32_e32 v87, v34
	v_pk_mov_b32 v[70:71], v[36:37], v[68:69] op_sel:[1,0]
	v_mov_b32_e32 v37, v69
	v_pk_mul_f32 v[68:69], v[90:91], v[90:91]
	v_pk_mul_f32 v[34:35], v[86:87], v[86:87]
	v_pk_add_f32 v[36:37], v[70:71], v[36:37]
	v_pk_mov_b32 v[70:71], v[34:35], v[68:69] op_sel:[1,0]
	v_mov_b32_e32 v35, v69
	v_pk_add_f32 v[34:35], v[70:71], v[34:35]
	v_fmac_f32_e32 v42, 0xba800000, v39
	v_pk_add_f32 v[34:35], v[34:35], v[34:35] op_sel_hi:[0,1]
	v_fmac_f32_e32 v43, 0xba800000, v39
	v_fmac_f32_e32 v40, 0xba800000, v39
	v_mul_f32_e32 v34, v42, v42
	v_fmac_f32_e32 v41, 0xba800000, v39
	v_pk_fma_f32 v[68:69], v[42:43], v[42:43], v[34:35] op_sel_hi:[1,1,0]
	v_mul_f32_e32 v34, v40, v40
	v_pk_add_f32 v[36:37], v[36:37], v[36:37] op_sel_hi:[0,1]
	v_pk_fma_f32 v[70:71], v[40:41], v[40:41], v[34:35] op_sel_hi:[1,1,0]
	v_fmac_f32_e32 v48, 0xba800000, v39
	v_fmac_f32_e32 v46, 0xba800000, v39
	v_fmac_f32_e32 v38, 0xba800000, v39
	v_fmac_f32_e32 v44, 0xba800000, v39
	v_mul_f32_e32 v68, v44, v44
	v_mul_f32_e32 v70, v38, v38
	v_mul_f32_e32 v36, v46, v46
	v_mul_f32_e32 v34, v48, v48
	v_pk_add_f32 v[68:69], v[68:69], v[70:71]
	v_pk_add_f32 v[34:35], v[36:37], v[34:35]
	v_mov_b32_e32 v47, v48
	v_pk_add_f32 v[34:35], v[68:69], v[34:35]
	s_nop 0
	v_add_f32_e32 v34, v34, v35
	s_nop 1
	v_add_f32_dpp v34, v34, v34 quad_perm:[1,0,3,2] row_mask:0xf bank_mask:0xf bound_ctrl:1
	s_nop 1
	v_add_f32_dpp v34, v34, v34 quad_perm:[2,3,0,1] row_mask:0xf bank_mask:0xf bound_ctrl:1
	s_nop 1
	v_add_f32_dpp v34, v34, v34 row_half_mirror row_mask:0xf bank_mask:0xf bound_ctrl:1
	s_nop 1
	v_add_f32_dpp v34, v34, v34 row_mirror row_mask:0xf bank_mask:0xf bound_ctrl:1
	s_nop 0
	v_readlane_b32 s19, v34, 16
	v_readlane_b32 s22, v34, 48
	v_readlane_b32 s0, v34, 0
	v_readlane_b32 s1, v34, 32
	v_mov_b32_e32 v34, s19
	v_mov_b32_e32 v35, s22
	v_pk_add_f32 v[34:35], s[0:1], v[34:35]
	s_mov_b32 s0, 0xf800000
	v_add_f32_e32 v34, v34, v35
	v_fmamk_f32 v34, v34, 0x3a800000, v83
	s_ashr_i32 s19, s18, 31
	v_mul_f32_e32 v35, 0x4f800000, v34
	v_cmp_gt_f32_e32 vcc, s0, v34
	s_lshl_b64 s[0:1], s[18:19], 11
	s_and_b32 s22, s30, 3
	v_cndmask_b32_e32 v36, v34, v35, vcc
	v_lshl_add_u64 v[34:35], v[54:55], 0, s[0:1]
	global_load_dwordx2 v[68:69], v[34:35], off
	global_load_dwordx2 v[70:71], v[34:35], off offset:512
	global_load_dwordx2 v[72:73], v[34:35], off offset:1024
	global_load_dwordx2 v[74:75], v[34:35], off offset:1536
	v_sqrt_f32_e32 v37, v36
	s_mul_i32 s26, s22, 0x810
	s_add_i32 s26, s87, s26
	v_add_u32_e32 v39, -1, v37
	v_fma_f32 v45, -v39, v37, v36
	v_cmp_ge_f32_e64 s[18:19], 0, v45
	v_add_u32_e32 v45, 1, v37
	s_nop 0
	v_cndmask_b32_e64 v39, v37, v39, s[18:19]
	v_fma_f32 v37, -v45, v37, v36
	v_cmp_lt_f32_e64 s[18:19], 0, v37
	s_nop 1
	v_cndmask_b32_e64 v37, v39, v45, s[18:19]
	v_mul_f32_e32 v39, 0x37800000, v37
	v_cndmask_b32_e32 v37, v37, v39, vcc
	v_cmp_class_f32_e32 vcc, v36, v84
	s_add_i32 s18, s4, s28
	s_ashr_i32 s19, s18, 31
	v_cndmask_b32_e32 v36, v37, v36, vcc
	v_div_scale_f32 v37, s[0:1], v36, v36, 1.0
	v_rcp_f32_e32 v39, v37
	s_lshl_b64 s[0:1], s[18:19], 11
	v_fma_f32 v34, -v37, v39, 1.0
	v_fmac_f32_e32 v39, v34, v39
	v_div_scale_f32 v34, vcc, 1.0, v36, 1.0
	v_mul_f32_e32 v35, v34, v39
	v_fma_f32 v45, -v37, v35, v34
	v_fmac_f32_e32 v35, v45, v39
	v_fma_f32 v34, -v37, v35, v34
	v_div_fmas_f32 v34, v34, v39, v35
	v_div_fixup_f32 v34, v34, v36, 1.0
	v_mov_b32_e32 v45, v38
	v_pk_mul_f32 v[36:37], v[76:77], v[34:35] op_sel_hi:[1,0]
	v_pk_mul_f32 v[76:77], v[88:89], v[34:35] op_sel_hi:[1,0]
	v_pk_mul_f32 v[38:39], v[44:45], v[34:35] op_sel_hi:[1,0]
	v_mov_b32_e32 v44, v78
	v_pk_fma_f32 v[76:77], v[4:5], v[76:77], v[12:13]
	v_pk_fma_f32 v[36:37], v[2:3], v[36:37], v[10:11]
	v_pk_mul_f32 v[86:87], v[86:87], v[34:35] op_sel_hi:[1,0]
	v_pk_mul_f32 v[88:89], v[90:91], v[34:35] op_sel_hi:[1,0]
	v_pk_fma_f32 v[86:87], v[6:7], v[86:87], v[14:15]
	v_pk_fma_f32 v[88:89], v[8:9], v[88:89], v[16:17]
	v_pk_mul_f32 v[42:43], v[42:43], v[34:35] op_sel_hi:[1,0]
	v_pk_mul_f32 v[40:41], v[40:41], v[34:35] op_sel_hi:[1,0]
	v_pk_mul_f32 v[34:35], v[46:47], v[34:35] op_sel_hi:[1,0]
	v_lshl_add_u32 v48, v44, 3, s26
	v_cvt_pk_bf16_f32 v44, v36, v37
	v_cvt_pk_bf16_f32 v45, v76, v77
	v_lshl_add_u64 v[46:47], v[56:57], 0, s[0:1]
	v_pk_fma_f32 v[40:41], v[20:21], v[40:41], v[28:29]
	v_pk_fma_f32 v[42:43], v[18:19], v[42:43], v[26:27]
	global_store_dwordx2 v[46:47], v[44:45], off
	ds_write_b64 v48, v[44:45] offset:33024
	v_cvt_pk_bf16_f32 v44, v86, v87
	v_cvt_pk_bf16_f32 v45, v88, v89
	v_pk_fma_f32 v[34:35], v[24:25], v[34:35], v[32:33]
	v_pk_fma_f32 v[38:39], v[22:23], v[38:39], v[30:31]
	global_store_dwordx2 v[46:47], v[44:45], off offset:512
	ds_write_b64 v48, v[44:45] offset:33536
	v_cvt_pk_bf16_f32 v44, v42, v43
	v_cvt_pk_bf16_f32 v45, v40, v41
	global_store_dwordx2 v[46:47], v[44:45], off offset:1024
	ds_write_b64 v48, v[44:45] offset:34048
	v_cvt_pk_bf16_f32 v44, v38, v39
	v_cvt_pk_bf16_f32 v45, v34, v35
	global_store_dwordx2 v[46:47], v[44:45], off offset:1536
	ds_write_b64 v48, v[44:45] offset:34560
	v_med3_f32 v36, v36, s8, v85
	v_med3_f32 v37, v37, s8, v85
	v_mov_b32_e32 v44, 0
	v_cvt_pk_fp8_f32 v44, v36, v37
	v_med3_f32 v36, v76, s8, v85
	v_med3_f32 v37, v77, s8, v85
	v_med3_f32 v45, v86, s8, v85
	v_cvt_pk_fp8_f32 v44, v36, v37 op_sel:[0,0,1]
	v_med3_f32 v46, v87, s8, v85
	v_mov_b32_e32 v47, 0
	v_cvt_pk_fp8_f32 v47, v45, v46
	s_lshl_b64 s[0:1], s[18:19], 10
	v_lshl_add_u64 v[36:37], v[58:59], 0, s[0:1]
	global_store_dword v[36:37], v44, off
	v_med3_f32 v44, v88, s8, v85
	v_med3_f32 v45, v89, s8, v85
	v_cvt_pk_fp8_f32 v47, v44, v45 op_sel:[0,0,1]
	v_med3_f32 v42, v42, s8, v85
	v_med3_f32 v43, v43, s8, v85
	v_mov_b32_e32 v44, 0
	v_cvt_pk_fp8_f32 v44, v42, v43
	v_med3_f32 v38, v38, s8, v85
	v_med3_f32 v39, v39, s8, v85
	v_mov_b32_e32 v42, 0
	v_cvt_pk_fp8_f32 v42, v38, v39
	v_med3_f32 v34, v34, s8, v85
	v_med3_f32 v35, v35, s8, v85
	v_med3_f32 v40, v40, s8, v85
	v_med3_f32 v41, v41, s8, v85
	v_cvt_pk_fp8_f32 v42, v34, v35 op_sel:[0,0,1]
	v_cvt_pk_fp8_f32 v44, v40, v41 op_sel:[0,0,1]
	s_cmp_lg_u32 s22, 3
	global_store_dword v[36:37], v47, off offset:256
	global_store_dword v[36:37], v44, off offset:512
	global_store_dword v[36:37], v42, off offset:768
	s_cbranch_scc1 .LBB0_2518
	v_mov_b32_e32 v76, v78
	s_nop 0
	v_and_b32_e32 v34, 3, v76
	v_mul_u32_u24_e32 v34, 0x810, v34
	v_and_b32_e32 v35, -16, v76
	v_add3_u32 v77, s87, v34, v35
	v_and_b32_e32 v34, 15, v76
	v_mul_u32_u24_e32 v34, 0x810, v34
	v_add3_u32 v94, 0, v34, v35
	ds_read_b128 v[34:37], v77 offset:33024
	ds_read_b128 v[38:41], v94
	s_waitcnt lgkmcnt(0)
	v_mfma_f32_16x16x32_bf16 v[34:37], v[34:37], v[38:41], 0
	ds_read_b128 v[38:41], v77 offset:33088
	ds_read_b128 v[42:45], v94 offset:64
	v_cmp_gt_i32_e32 vcc, 16, v76
	s_waitcnt lgkmcnt(0)
	v_mfma_f32_16x16x32_bf16 v[38:41], v[38:41], v[42:45], 0
	ds_read_b128 v[42:45], v77 offset:33152
	ds_read_b128 v[46:49], v94 offset:128
	s_waitcnt lgkmcnt(0)
	v_mfma_f32_16x16x32_bf16 v[42:45], v[42:45], v[46:49], 0
	ds_read_b128 v[46:49], v77 offset:33216
	ds_read_b128 v[86:89], v94 offset:192
	s_waitcnt lgkmcnt(0)
	v_mfma_f32_16x16x32_bf16 v[46:49], v[46:49], v[86:89], 0
	ds_read_b128 v[86:89], v77 offset:33280
	ds_read_b128 v[90:93], v94 offset:256
	s_waitcnt lgkmcnt(0)
	v_mfma_f32_16x16x32_bf16 v[34:37], v[86:89], v[90:93], v[34:37]
	ds_read_b128 v[86:89], v77 offset:33344
	ds_read_b128 v[90:93], v94 offset:320
	s_waitcnt lgkmcnt(0)
	v_mfma_f32_16x16x32_bf16 v[38:41], v[86:89], v[90:93], v[38:41]
	ds_read_b128 v[86:89], v77 offset:33408
	ds_read_b128 v[90:93], v94 offset:384
	s_waitcnt lgkmcnt(0)
	v_mfma_f32_16x16x32_bf16 v[42:45], v[86:89], v[90:93], v[42:45]
	ds_read_b128 v[86:89], v77 offset:33472
	ds_read_b128 v[90:93], v94 offset:448
	s_waitcnt lgkmcnt(0)
	v_mfma_f32_16x16x32_bf16 v[46:49], v[86:89], v[90:93], v[46:49]
	ds_read_b128 v[86:89], v77 offset:33536
	ds_read_b128 v[90:93], v94 offset:512
	s_waitcnt lgkmcnt(0)
	v_mfma_f32_16x16x32_bf16 v[34:37], v[86:89], v[90:93], v[34:37]
	ds_read_b128 v[86:89], v77 offset:33600
	ds_read_b128 v[90:93], v94 offset:576
	s_waitcnt lgkmcnt(0)
	v_mfma_f32_16x16x32_bf16 v[38:41], v[86:89], v[90:93], v[38:41]
	ds_read_b128 v[86:89], v77 offset:33664
	ds_read_b128 v[90:93], v94 offset:640
	s_waitcnt lgkmcnt(0)
	v_mfma_f32_16x16x32_bf16 v[42:45], v[86:89], v[90:93], v[42:45]
	ds_read_b128 v[86:89], v77 offset:33728
	ds_read_b128 v[90:93], v94 offset:704
	s_waitcnt lgkmcnt(0)
	v_mfma_f32_16x16x32_bf16 v[46:49], v[86:89], v[90:93], v[46:49]
	ds_read_b128 v[86:89], v77 offset:33792
	ds_read_b128 v[90:93], v94 offset:768
	s_waitcnt lgkmcnt(0)
	v_mfma_f32_16x16x32_bf16 v[34:37], v[86:89], v[90:93], v[34:37]
	ds_read_b128 v[86:89], v77 offset:33856
	ds_read_b128 v[90:93], v94 offset:832
	s_waitcnt lgkmcnt(0)
	v_mfma_f32_16x16x32_bf16 v[38:41], v[86:89], v[90:93], v[38:41]
	ds_read_b128 v[86:89], v77 offset:33920
	ds_read_b128 v[90:93], v94 offset:896
	s_waitcnt lgkmcnt(0)
	v_mfma_f32_16x16x32_bf16 v[42:45], v[86:89], v[90:93], v[42:45]
	ds_read_b128 v[86:89], v77 offset:33984
	ds_read_b128 v[90:93], v94 offset:960
	s_waitcnt lgkmcnt(0)
	v_mfma_f32_16x16x32_bf16 v[46:49], v[86:89], v[90:93], v[46:49]
	ds_read_b128 v[86:89], v77 offset:34048
	ds_read_b128 v[90:93], v94 offset:1024
	s_waitcnt lgkmcnt(0)
	v_mfma_f32_16x16x32_bf16 v[34:37], v[86:89], v[90:93], v[34:37]
	ds_read_b128 v[86:89], v77 offset:34112
	ds_read_b128 v[90:93], v94 offset:1088
	s_waitcnt lgkmcnt(0)
	v_mfma_f32_16x16x32_bf16 v[38:41], v[86:89], v[90:93], v[38:41]
	ds_read_b128 v[86:89], v77 offset:34176
	ds_read_b128 v[90:93], v94 offset:1152
	s_waitcnt lgkmcnt(0)
	v_mfma_f32_16x16x32_bf16 v[42:45], v[86:89], v[90:93], v[42:45]
	ds_read_b128 v[86:89], v77 offset:34240
	ds_read_b128 v[90:93], v94 offset:1216
	s_waitcnt lgkmcnt(0)
	v_mfma_f32_16x16x32_bf16 v[46:49], v[86:89], v[90:93], v[46:49]
	ds_read_b128 v[86:89], v77 offset:34304
	ds_read_b128 v[90:93], v94 offset:1280
	s_waitcnt lgkmcnt(0)
	v_mfma_f32_16x16x32_bf16 v[34:37], v[86:89], v[90:93], v[34:37]
	ds_read_b128 v[86:89], v77 offset:34368
	ds_read_b128 v[90:93], v94 offset:1344
	s_waitcnt lgkmcnt(0)
	v_mfma_f32_16x16x32_bf16 v[38:41], v[86:89], v[90:93], v[38:41]
	ds_read_b128 v[86:89], v77 offset:34432
	ds_read_b128 v[90:93], v94 offset:1408
	s_waitcnt lgkmcnt(0)
	v_mfma_f32_16x16x32_bf16 v[42:45], v[86:89], v[90:93], v[42:45]
	ds_read_b128 v[86:89], v77 offset:34496
	ds_read_b128 v[90:93], v94 offset:1472
	s_waitcnt lgkmcnt(0)
	v_mfma_f32_16x16x32_bf16 v[46:49], v[86:89], v[90:93], v[46:49]
	ds_read_b128 v[86:89], v77 offset:34560
	ds_read_b128 v[90:93], v94 offset:1536
	s_waitcnt lgkmcnt(0)
	v_mfma_f32_16x16x32_bf16 v[34:37], v[86:89], v[90:93], v[34:37]
	ds_read_b128 v[86:89], v77 offset:34624
	ds_read_b128 v[90:93], v94 offset:1600
	s_waitcnt lgkmcnt(0)
	v_mfma_f32_16x16x32_bf16 v[38:41], v[86:89], v[90:93], v[38:41]
	ds_read_b128 v[86:89], v77 offset:34688
	ds_read_b128 v[90:93], v94 offset:1664
	s_waitcnt lgkmcnt(0)
	v_mfma_f32_16x16x32_bf16 v[42:45], v[86:89], v[90:93], v[42:45]
	ds_read_b128 v[86:89], v77 offset:34752
	ds_read_b128 v[90:93], v94 offset:1728
	s_waitcnt lgkmcnt(0)
	v_mfma_f32_16x16x32_bf16 v[46:49], v[86:89], v[90:93], v[46:49]
	ds_read_b128 v[86:89], v77 offset:34816
	ds_read_b128 v[90:93], v94 offset:1792
	s_waitcnt lgkmcnt(0)
	v_mfma_f32_16x16x32_bf16 v[34:37], v[86:89], v[90:93], v[34:37]
	ds_read_b128 v[86:89], v77 offset:34880
	ds_read_b128 v[90:93], v94 offset:1856
	s_waitcnt lgkmcnt(0)
	v_mfma_f32_16x16x32_bf16 v[38:41], v[86:89], v[90:93], v[38:41]
	ds_read_b128 v[86:89], v77 offset:34944
	ds_read_b128 v[90:93], v94 offset:1920
	s_waitcnt lgkmcnt(0)
	v_mfma_f32_16x16x32_bf16 v[42:45], v[86:89], v[90:93], v[42:45]
	ds_read_b128 v[86:89], v77 offset:35008
	ds_read_b128 v[90:93], v94 offset:1984
	s_nop 1
	v_pk_add_f32 v[34:35], v[34:35], v[38:39]
	v_ashrrev_i32_e32 v77, 31, v76
	s_waitcnt lgkmcnt(0)
	v_mfma_f32_16x16x32_bf16 v[46:49], v[86:89], v[90:93], v[46:49]
	s_nop 7
	v_pk_add_f32 v[38:39], v[42:43], v[46:47]
	s_nop 0
	v_pk_add_f32 v[38:39], v[34:35], v[38:39]
	v_lshlrev_b64 v[34:35], 13, v[76:77]
	v_lshl_add_u64 v[34:35], s[24:25], 0, v[34:35]
	v_mov_b32_dpp v42, v38 quad_perm:[1,0,3,2] row_mask:0xf bank_mask:0xf bound_ctrl:1
	v_max_f32_e32 v42, v42, v42
	v_max_f32_e32 v42, v38, v42
	s_nop 1
	v_mov_b32_dpp v43, v42 quad_perm:[2,3,0,1] row_mask:0xf bank_mask:0xf bound_ctrl:1
	v_max_f32_e32 v43, v43, v43
	v_max_f32_e32 v42, v42, v43
	s_nop 1
	v_mov_b32_dpp v43, v42 row_half_mirror row_mask:0xf bank_mask:0xf bound_ctrl:1
	v_max_f32_e32 v43, v43, v43
	v_max_f32_e32 v42, v42, v43
	s_nop 1
	v_mov_b32_dpp v43, v42 row_mirror row_mask:0xf bank_mask:0xf bound_ctrl:1
	v_max_f32_e32 v43, v43, v43
	v_max_f32_e32 v42, v42, v43
	v_sub_f32_e32 v38, v38, v42
	v_mul_f32_e32 v38, 0x3fb8aa3b, v38
	v_exp_f32_e32 v38, v38
	s_nop 1
	v_add_f32_dpp v42, v38, v38 quad_perm:[1,0,3,2] row_mask:0xf bank_mask:0xf bound_ctrl:1
	s_nop 1
	v_add_f32_dpp v42, v42, v42 quad_perm:[2,3,0,1] row_mask:0xf bank_mask:0xf bound_ctrl:1
	s_nop 1
	v_add_f32_dpp v42, v42, v42 row_half_mirror row_mask:0xf bank_mask:0xf bound_ctrl:1
	s_nop 1
	v_mov_b32_dpp v43, v42 row_mirror row_mask:0xf bank_mask:0xf bound_ctrl:1
	s_and_saveexec_b64 s[26:27], vcc
	s_cbranch_execz .LBB0_2522
	v_add_f32_e32 v42, v42, v43
	v_rcp_f32_e32 v42, v42
	s_sub_i32 s19, s18, 24
	s_ashr_i32 s0, s19, 11
	s_ashr_i32 s1, s0, 31
	s_and_b32 s19, s19, 0x7ff
	s_lshl_b64 s[0:1], s[0:1], 17
	v_mul_f32_e32 v38, v38, v42
	v_lshl_add_u64 v[42:43], v[34:35], 0, s[0:1]
	s_lshl_b32 s22, s19, 2
	v_lshl_add_u64 v[42:43], v[42:43], 0, s[22:23]
	global_store_dword v[42:43], v38, off

.LBB0_2582:
	s_or_b64 exec, exec, s[30:31]
	v_cndmask_b32_e64 v2, -1, v3, s[50:51]
	v_cndmask_b32_e64 v12, -1, v5, s[56:57]
	v_cndmask_b32_e64 v3, -1, v6, s[58:59]
	v_cndmask_b32_e64 v6, -1, v7, s[52:53]
	v_cndmask_b32_e64 v4, -1, v8, s[46:47]
	v_cndmask_b32_e64 v7, -1, v9, s[42:43]
	v_cndmask_b32_e64 v5, -1, v10, s[38:39]
	v_cndmask_b32_e64 v8, -1, v11, s[28:29]
	s_add_i32 s88, s88, s90
	v_perm_b32 v5, v8, v5, s4
	v_perm_b32 v4, v7, v4, s4
	v_perm_b32 v3, v6, v3, s4
	v_perm_b32 v2, v12, v2, s4
	v_lshl_add_u64 v[6:7], v[18:19], 1, v[16:17]
	s_cmpk_lt_i32 s88, 0x200
	global_store_dwordx4 v[6:7], v[2:5], off
	s_waitcnt lgkmcnt(0)
	s_barrier
	s_cbranch_scc0 .LBB0_2630
.LBB0_2583:
	v_add_u32_e32 v22, s88, v24
	v_ashrrev_i32_e32 v23, 31, v22
	v_lshlrev_b64 v[2:3], 13, v[22:23]
	v_lshl_add_u64 v[2:3], v[14:15], 0, v[2:3]
	global_load_dwordx4 v[6:9], v[2:3], off
	s_nop 0
	global_load_dwordx4 v[2:5], v[2:3], off offset:16
	v_lshlrev_b64 v[18:19], 11, v[22:23]
	v_mov_b32_e32 v21, 0x100
	s_mov_b32 s0, 24
	v_mov_b32_e32 v20, 0
	s_mov_b32 s1, 0
	s_branch .LBB0_2586

.LBB0_2612:
	s_or_b64 exec, exec, s[62:63]
	v_sub_u32_e32 v2, v3, v2
	s_waitcnt lgkmcnt(0)
	v_add_u32_e32 v2, v2, v5
	v_add3_u32 v5, v2, v4, v6
	v_lshlrev_b32_e32 v4, 5, v22
	v_ashrrev_i32_e32 v3, 4, v22
	v_and_b32_e32 v4, 0x1e0, v4
	v_cmp_lt_i32_sdwa s[0:1], v5, v21 src0_sel:WORD_1 src1_sel:DWORD
	v_lshl_or_b32 v2, v3, 11, v28
	v_add_lshl_u32 v4, v4, v3, 8
	s_and_b64 s[0:1], s[56:57], s[0:1]
	v_min_i32_sdwa v3, v5, v21 dst_sel:DWORD dst_unused:UNUSED_PAD src0_sel:WORD_1 src1_sel:DWORD
	s_or_b64 s[50:51], s[50:51], s[0:1]
	v_add_u32_sdwa v3, v3, v5 dst_sel:DWORD dst_unused:UNUSED_PAD src0_sel:DWORD src1_sel:WORD_0
	s_and_saveexec_b64 s[62:63], s[50:51]
	s_cbranch_execz .LBB0_2614
	v_add_u32_e32 v6, v3, v4
	v_ashrrev_i32_e32 v7, 31, v6
	v_lshl_add_u64 v[6:7], v[6:7], 2, s[64:65]
	global_store_dword v[6:7], v2, off
.LBB0_2614:
	s_or_b64 exec, exec, s[62:63]
	v_cndmask_b32_e64 v7, 0, 1, s[56:57]
	v_add_u32_sdwa v7, v5, v7 dst_sel:DWORD dst_unused:UNUSED_PAD src0_sel:WORD_1 src1_sel:DWORD
	v_cmp_lt_i32_e64 s[56:57], v7, v21
	v_add_u32_sdwa v6, v5, v10 dst_sel:DWORD dst_unused:UNUSED_PAD src0_sel:WORD_0 src1_sel:DWORD
	s_and_b64 s[0:1], s[58:59], s[56:57]
	v_min_i32_e32 v5, v7, v21
	s_or_b64 s[56:57], s[60:61], s[0:1]
	v_add_u32_e32 v5, v5, v6
	s_and_saveexec_b64 s[62:63], s[56:57]
	s_cbranch_execz .LBB0_2616
	v_add_u32_e32 v8, v5, v4
	v_ashrrev_i32_e32 v9, 31, v8
	v_lshl_add_u64 v[8:9], v[8:9], 2, s[64:65]
	v_or_b32_e32 v10, 1, v2
	global_store_dword v[8:9], v10, off
.LBB0_2616:
	s_or_b64 exec, exec, s[62:63]
	v_cndmask_b32_e64 v8, 0, 1, s[60:61]
	v_add_u32_e32 v8, v6, v8
	v_cndmask_b32_e64 v6, 0, 1, s[58:59]
	v_add_u32_e32 v7, v7, v6
	v_cmp_lt_i32_e64 s[58:59], v7, v21
	s_and_b64 s[0:1], s[52:53], s[58:59]
	v_min_i32_e32 v6, v7, v21
	s_or_b64 s[58:59], s[54:55], s[0:1]
	v_add_u32_e32 v6, v6, v8
	s_and_saveexec_b64 s[60:61], s[58:59]
	s_cbranch_execz .LBB0_2618
	v_add_u32_e32 v10, v6, v4
	v_ashrrev_i32_e32 v11, 31, v10
	v_lshl_add_u64 v[10:11], v[10:11], 2, s[64:65]
	v_or_b32_e32 v9, 2, v2
	global_store_dword v[10:11], v9, off
.LBB0_2618:
	s_or_b64 exec, exec, s[60:61]
	v_cndmask_b32_e64 v9, 0, 1, s[54:55]
	v_add_u32_e32 v8, v8, v9
	v_cndmask_b32_e64 v9, 0, 1, s[52:53]
	v_add_u32_e32 v9, v7, v9
	v_cmp_lt_i32_e64 s[52:53], v9, v21
	s_and_b64 s[0:1], s[46:47], s[52:53]
	v_min_i32_e32 v7, v9, v21
	s_or_b64 s[52:53], s[48:49], s[0:1]
	v_add_u32_e32 v7, v7, v8
	s_and_saveexec_b64 s[54:55], s[52:53]
	s_cbranch_execz .LBB0_2620
	v_add_u32_e32 v10, v7, v4
	v_ashrrev_i32_e32 v11, 31, v10
	v_lshl_add_u64 v[10:11], v[10:11], 2, s[64:65]
	v_or_b32_e32 v12, 3, v2
	global_store_dword v[10:11], v12, off
.LBB0_2620:
	s_or_b64 exec, exec, s[54:55]
	v_cndmask_b32_e64 v10, 0, 1, s[48:49]
	v_add_u32_e32 v10, v8, v10
	v_cndmask_b32_e64 v8, 0, 1, s[46:47]
	v_add_u32_e32 v9, v9, v8
	v_cmp_lt_i32_e64 s[46:47], v9, v21
	s_and_b64 s[0:1], s[42:43], s[46:47]
	v_min_i32_e32 v8, v9, v21
	s_or_b64 s[46:47], s[44:45], s[0:1]
	v_add_u32_e32 v8, v8, v10
	s_and_saveexec_b64 s[48:49], s[46:47]
	s_cbranch_execz .LBB0_2622
	v_add_u32_e32 v22, v8, v4
	v_ashrrev_i32_e32 v23, 31, v22
	v_lshl_add_u64 v[22:23], v[22:23], 2, s[64:65]
	v_or_b32_e32 v11, 4, v2
	global_store_dword v[22:23], v11, off
.LBB0_2622:
	s_or_b64 exec, exec, s[48:49]
	v_cndmask_b32_e64 v11, 0, 1, s[44:45]
	v_add_u32_e32 v10, v10, v11
	v_cndmask_b32_e64 v11, 0, 1, s[42:43]
	v_add_u32_e32 v12, v9, v11
	v_cmp_lt_i32_e64 s[42:43], v12, v21
	s_and_b64 s[0:1], s[38:39], s[42:43]
	v_min_i32_e32 v9, v12, v21
	s_or_b64 s[42:43], s[40:41], s[0:1]
	v_add_u32_e32 v9, v9, v10
	s_and_saveexec_b64 s[44:45], s[42:43]
	s_cbranch_execz .LBB0_2624
	v_add_u32_e32 v22, v9, v4
	v_ashrrev_i32_e32 v23, 31, v22
	v_lshl_add_u64 v[22:23], v[22:23], 2, s[64:65]
	v_or_b32_e32 v11, 5, v2
	global_store_dword v[22:23], v11, off
.LBB0_2624:
	s_or_b64 exec, exec, s[44:45]
	v_cndmask_b32_e64 v11, 0, 1, s[40:41]
	v_add_u32_e32 v11, v10, v11
	v_cndmask_b32_e64 v10, 0, 1, s[38:39]
	v_add_u32_e32 v12, v12, v10
	v_cmp_lt_i32_e64 s[38:39], v12, v21
	s_and_b64 s[0:1], s[28:29], s[38:39]
	v_min_i32_e32 v10, v12, v21
	s_or_b64 s[38:39], s[34:35], s[0:1]
	v_add_u32_e32 v10, v10, v11
	s_and_saveexec_b64 s[40:41], s[38:39]
	s_cbranch_execz .LBB0_2626
	v_add_u32_e32 v22, v10, v4
	v_ashrrev_i32_e32 v23, 31, v22
	v_lshl_add_u64 v[22:23], v[22:23], 2, s[64:65]
	v_or_b32_e32 v20, 6, v2
	global_store_dword v[22:23], v20, off
.LBB0_2626:
	s_or_b64 exec, exec, s[40:41]
	v_cndmask_b32_e64 v22, 0, 1, s[28:29]
	v_add_u32_e32 v12, v12, v22
	v_cmp_lt_i32_e64 s[28:29], v12, v21
	v_cndmask_b32_e64 v20, 0, 1, s[34:35]
	s_and_b64 s[0:1], s[30:31], s[28:29]
	v_min_i32_e32 v12, v12, v21
	s_or_b64 s[28:29], s[36:37], s[0:1]
	v_add3_u32 v11, v11, v20, v12
	s_and_saveexec_b64 s[30:31], s[28:29]
	s_cbranch_execz .LBB0_2582
	v_add_u32_e32 v20, v11, v4
	v_ashrrev_i32_e32 v21, 31, v20
	v_lshl_add_u64 v[20:21], v[20:21], 2, s[64:65]
	v_or_b32_e32 v2, 7, v2
	global_store_dword v[20:21], v2, off
	s_branch .LBB0_2582

.LBB0_2686:
	s_sub_i32 s0, 0x200, s38
	s_min_i32 s41, s0, s90
	s_lshl_b32 s22, s41, 3
	s_ashr_i32 s23, s22, 31
	v_mov_b32_e32 v2, v0
	s_cmp_lt_i32 s2, s22
	s_cselect_b64 s[12:13], -1, 0
	s_cmp_ge_i32 s2, s22
	v_readfirstlane_b32 s42, v2
	s_cbranch_scc1 .LBB0_2734
	s_movk_i32 s0, 0xff
	v_cmp_lt_i32_e64 s[6:7], s0, v2
	s_movk_i32 s0, 0x100
	v_lshl_add_u32 v3, v2, 2, s95
	v_cmp_gt_i32_e64 s[10:11], s0, v2
	s_and_saveexec_b64 s[24:25], s[10:11]
	s_cbranch_execz .LBB0_2689
	s_or_b32 s0, s41, s80
	s_mul_i32 s0, s0, s76
	s_add_i32 s0, s0, s91
	s_ashr_i32 s1, s0, 31
	s_lshr_b32 s1, s1, 26
	s_add_i32 s1, s0, s1
	s_ashr_i32 s26, s1, 6
	s_lshl_b32 s26, s26, 3
	s_sub_i32 s27, s41, s26
	s_min_i32 s27, s27, 8
	s_abs_i32 s27, s27
	v_cvt_f32_u32_e32 v4, s27
	s_sub_i32 s28, 0, s27
	s_andn2_b32 s1, s1, 63
	s_sub_i32 s0, s0, s1
	v_rcp_iflag_f32_e32 v4, v4
	s_ashr_i32 s1, s0, 31
	s_abs_i32 s0, s0
	v_mul_f32_e32 v4, 0x4f7ffffe, v4
	v_cvt_u32_f32_e32 v4, v4
	s_nop 0
	v_readfirstlane_b32 s29, v4
	s_mul_i32 s28, s28, s29
	s_mul_hi_u32 s28, s29, s28
	s_add_i32 s29, s29, s28
	s_mul_hi_u32 s28, s0, s29
	s_mul_i32 s28, s28, s27
	s_sub_i32 s0, s0, s28
	s_sub_i32 s28, s0, s27
	s_cmp_ge_u32 s0, s27
	s_cselect_b32 s0, s28, s0
	s_sub_i32 s28, s0, s27
	s_cmp_ge_u32 s0, s27
	s_cselect_b32 s0, s28, s0
	s_xor_b32 s0, s0, s1
	s_sub_i32 s0, s0, s1
	s_add_i32 s1, s26, s38
	s_add_i32 s1, s1, s0
	v_lshl_add_u32 v4, s1, 8, v2
	v_ashrrev_i32_e32 v5, 31, v4
	v_lshl_add_u64 v[4:5], v[4:5], 2, s[16:17]
	global_load_dword v4, v[4:5], off
	s_waitcnt vmcnt(0) lgkmcnt(0)
	v_lshlrev_b32_e32 v4, 10, v4
	ds_write_b32 v3, v4

.LBB0_2731:
	s_or_b64 exec, exec, s[24:25]
	v_readlane_b32 s0, v253, 27
	v_mov_b64_e32 v[4:5], s[22:23]
	v_readlane_b32 s1, v253, 28
	s_nop 1
	v_cmp_lt_i64_e32 vcc, s[0:1], v[4:5]
	s_xor_b64 s[0:1], s[6:7], -1
	s_and_b64 s[0:1], vcc, s[0:1]
	s_and_saveexec_b64 s[6:7], s[0:1]
	s_cbranch_execz .LBB0_2733
	v_readlane_b32 s0, v253, 30
	s_or_b32 s0, s41, s0
	v_readlane_b32 s1, v253, 29
	s_mul_i32 s0, s0, s1
	v_readlane_b32 s1, v253, 26
	s_add_i32 s0, s0, s1
	s_ashr_i32 s1, s0, 31
	s_lshr_b32 s1, s1, 26
	s_add_i32 s1, s0, s1
	s_ashr_i32 s10, s1, 6
	s_lshl_b32 s10, s10, 3
	s_sub_i32 s11, s41, s10
	s_min_i32 s11, s11, 8
	s_abs_i32 s11, s11
	v_cvt_f32_u32_e32 v4, s11
	s_sub_i32 s24, 0, s11
	s_andn2_b32 s1, s1, 63
	s_sub_i32 s0, s0, s1
	v_rcp_iflag_f32_e32 v4, v4
	s_ashr_i32 s1, s0, 31
	s_abs_i32 s0, s0
	v_mul_f32_e32 v4, 0x4f7ffffe, v4
	v_cvt_u32_f32_e32 v4, v4
	s_nop 0
	v_readfirstlane_b32 s25, v4
	s_mul_i32 s24, s24, s25
	s_mul_hi_u32 s24, s25, s24
	s_add_i32 s25, s25, s24
	s_mul_hi_u32 s24, s0, s25
	s_mul_i32 s24, s24, s11
	s_sub_i32 s0, s0, s24
	s_sub_i32 s24, s0, s11
	s_cmp_ge_u32 s0, s11
	s_cselect_b32 s0, s24, s0
	s_sub_i32 s24, s0, s11
	s_cmp_ge_u32 s0, s11
	s_cselect_b32 s0, s24, s0
	s_xor_b32 s0, s0, s1
	s_sub_i32 s0, s0, s1
	s_add_i32 s1, s10, s38
	s_add_i32 s1, s1, s0
	v_lshl_add_u32 v4, s1, 8, v2
	v_ashrrev_i32_e32 v5, 31, v4
	v_lshl_add_u64 v[4:5], v[4:5], 2, s[16:17]
	global_load_dword v4, v[4:5], off
	s_waitcnt vmcnt(0) lgkmcnt(0)
	v_lshlrev_b32_e32 v4, 10, v4
	ds_write_b32 v3, v4 offset:15360

.LBB0_2749:
	s_add_u32 s10, s34, 0x100
	s_addc_u32 s11, s35, 0
	s_add_u32 s30, s29, s34
	s_addc_u32 s31, s55, s35
	s_cmpk_eq_i32 s34, 0x300
	s_cselect_b64 vcc, -1, 0
	s_and_b64 s[0:1], vcc, exec
	s_cselect_b32 s1, 0, s10
	s_cselect_b32 s0, 0, s11
	s_cselect_b32 s30, s27, s30
	s_cselect_b32 s31, s25, s31
	s_add_u32 s36, s14, s1
	s_addc_u32 s37, s15, s0
	s_add_i32 s1, 0, 0x10000
	v_add_u32_e32 v14, s1, v196
	ds_read_b128 v[2:5], v14
	ds_read_b128 v[6:9], v14 offset:1024
	ds_read_b128 v[10:13], v14 offset:2048
	ds_read_b128 v[14:17], v14 offset:3072
	v_cndmask_b32_e32 v162, v168, v171, vcc
	v_cndmask_b32_e32 v184, v170, v197, vcc
	v_cndmask_b32_e32 v175, v172, v198, vcc
	v_cndmask_b32_e32 v173, v174, v199, vcc
	v_lshl_add_u64 v[18:19], v[178:179], 0, s[34:35]
	s_add_i32 m0, s45, 0xc000
	ds_read_b128 v[200:203], v169
	ds_read_b128 v[204:207], v169 offset:1024
	ds_read_b128 v[208:211], v169 offset:2048
	ds_read_b128 v[212:215], v169 offset:3072
	ds_read_b128 v[216:219], v169 offset:4096
	ds_read_b128 v[220:223], v169 offset:5120
	ds_read_b128 v[224:227], v169 offset:6144
	ds_read_b128 v[228:231], v169 offset:7168
	global_load_lds_dwordx4 v[18:19], off
	v_lshl_add_u64 v[18:19], v[176:177], 0, s[34:35]
	s_add_i32 m0, s45, 0xe000
	s_nop 0
	global_load_lds_dwordx4 v[18:19], off
	s_waitcnt lgkmcnt(8)
	s_waitcnt vmcnt(10)
	s_barrier
	s_waitcnt lgkmcnt(0)
	s_waitcnt lgkmcnt(0)
	v_mfma_scale_f32_16x16x128_f8f6f4 v[158:161], v[2:9], v[200:207], v[158:161], v1, v1 op_sel_hi:[0,0,0]
	v_mfma_scale_f32_16x16x128_f8f6f4 v[150:153], v[10:17], v[200:207], v[150:153], v1, v1 op_sel_hi:[0,0,0]
	v_mfma_scale_f32_16x16x128_f8f6f4 v[142:145], v[2:9], v[208:215], v[142:145], v1, v1 op_sel_hi:[0,0,0]
	v_mfma_scale_f32_16x16x128_f8f6f4 v[134:137], v[10:17], v[208:215], v[134:137], v1, v1 op_sel_hi:[0,0,0]
	v_mfma_scale_f32_16x16x128_f8f6f4 v[126:129], v[2:9], v[216:223], v[126:129], v1, v1 op_sel_hi:[0,0,0]
	v_mfma_scale_f32_16x16x128_f8f6f4 v[118:121], v[10:17], v[216:223], v[118:121], v1, v1 op_sel_hi:[0,0,0]
	v_mfma_scale_f32_16x16x128_f8f6f4 v[110:113], v[2:9], v[224:231], v[110:113], v1, v1 op_sel_hi:[0,0,0]
	v_mfma_scale_f32_16x16x128_f8f6f4 v[102:105], v[10:17], v[224:231], v[102:105], v1, v1 op_sel_hi:[0,0,0]
	s_barrier
	s_add_i32 s0, 0, 0x14000
	s_add_i32 s1, s1, s43
	v_add_u32_e32 v30, s0, v196
	v_lshl_add_u64 v[180:181], s[30:31], 0, v[164:165]
	s_mov_b32 m0, s1
	ds_read_b128 v[18:21], v30
	ds_read_b128 v[22:25], v30 offset:1024
	ds_read_b128 v[26:29], v30 offset:2048
	ds_read_b128 v[30:33], v30 offset:3072
	global_load_lds_dwordx4 v[180:181], off
	v_lshl_add_u64 v[182:183], s[30:31], 0, v[166:167]
	s_add_i32 m0, s1, 0x2000
	s_nop 0
	global_load_lds_dwordx4 v[182:183], off
	s_waitcnt vmcnt(10)
	s_barrier
	s_waitcnt lgkmcnt(0)
	s_waitcnt lgkmcnt(0)
	v_mfma_scale_f32_16x16x128_f8f6f4 v[154:157], v[18:25], v[200:207], v[154:157], v1, v1 op_sel_hi:[0,0,0]
	v_mfma_scale_f32_16x16x128_f8f6f4 v[146:149], v[26:33], v[200:207], v[146:149], v1, v1 op_sel_hi:[0,0,0]
	v_mfma_scale_f32_16x16x128_f8f6f4 v[138:141], v[18:25], v[208:215], v[138:141], v1, v1 op_sel_hi:[0,0,0]
	v_mfma_scale_f32_16x16x128_f8f6f4 v[130:133], v[26:33], v[208:215], v[130:133], v1, v1 op_sel_hi:[0,0,0]
	v_mfma_scale_f32_16x16x128_f8f6f4 v[122:125], v[18:25], v[216:223], v[122:125], v1, v1 op_sel_hi:[0,0,0]
	v_mfma_scale_f32_16x16x128_f8f6f4 v[114:117], v[26:33], v[216:223], v[114:117], v1, v1 op_sel_hi:[0,0,0]
	v_mfma_scale_f32_16x16x128_f8f6f4 v[106:109], v[18:25], v[224:231], v[106:109], v1, v1 op_sel_hi:[0,0,0]
	v_mfma_scale_f32_16x16x128_f8f6f4 v[98:101], v[26:33], v[224:231], v[98:101], v1, v1 op_sel_hi:[0,0,0]
	s_mov_b32 m0, s45
	s_barrier
	ds_read_b128 v[200:203], v169 offset:16384
	ds_read_b128 v[204:207], v169 offset:17408
	ds_read_b128 v[208:211], v169 offset:18432
	ds_read_b128 v[212:215], v169 offset:19456
	ds_read_b128 v[216:219], v169 offset:20480
	ds_read_b128 v[220:223], v169 offset:21504
	ds_read_b128 v[224:227], v169 offset:22528
	ds_read_b128 v[228:231], v169 offset:23552
	global_load_lds_dwordx4 v162, s[36:37]
	s_mov_b32 m0, s46
	v_mov_b32_e32 v185, v163
	global_load_lds_dwordx4 v184, s[36:37]
	s_waitcnt vmcnt(10)
	s_barrier
	s_waitcnt lgkmcnt(0)
	v_lshl_add_u64 v[186:187], s[36:37], 0, v[162:163]
	v_lshl_add_u64 v[184:185], s[36:37], 0, v[184:185]
	s_waitcnt lgkmcnt(0)
	v_mfma_scale_f32_16x16x128_f8f6f4 v[94:97], v[2:9], v[200:207], v[94:97], v1, v1 op_sel_hi:[0,0,0]
	v_mfma_scale_f32_16x16x128_f8f6f4 v[86:89], v[10:17], v[200:207], v[86:89], v1, v1 op_sel_hi:[0,0,0]
	v_mfma_scale_f32_16x16x128_f8f6f4 v[78:81], v[2:9], v[208:215], v[78:81], v1, v1 op_sel_hi:[0,0,0]
	v_mfma_scale_f32_16x16x128_f8f6f4 v[70:73], v[10:17], v[208:215], v[70:73], v1, v1 op_sel_hi:[0,0,0]
	v_mfma_scale_f32_16x16x128_f8f6f4 v[62:65], v[2:9], v[216:223], v[62:65], v1, v1 op_sel_hi:[0,0,0]
	v_mfma_scale_f32_16x16x128_f8f6f4 v[54:57], v[10:17], v[216:223], v[54:57], v1, v1 op_sel_hi:[0,0,0]
	v_mfma_scale_f32_16x16x128_f8f6f4 v[46:49], v[2:9], v[224:231], v[46:49], v1, v1 op_sel_hi:[0,0,0]
	v_mfma_scale_f32_16x16x128_f8f6f4 v[38:41], v[10:17], v[224:231], v[38:41], v1, v1 op_sel_hi:[0,0,0]
	s_barrier
	s_add_u32 s34, s30, 0x20000
	s_addc_u32 s35, s31, 0
	s_add_i32 s0, s0, s43
	v_lshl_add_u64 v[2:3], s[34:35], 0, v[164:165]
	s_mov_b32 m0, s0
	s_nop 0
	global_load_lds_dwordx4 v[2:3], off
	v_lshl_add_u64 v[2:3], s[34:35], 0, v[166:167]
	s_add_i32 m0, s0, 0x2000
	s_nop 0
	global_load_lds_dwordx4 v[2:3], off
	s_waitcnt vmcnt(10)
	s_barrier
	v_mfma_scale_f32_16x16x128_f8f6f4 v[90:93], v[18:25], v[200:207], v[90:93], v1, v1 op_sel_hi:[0,0,0]
	v_mfma_scale_f32_16x16x128_f8f6f4 v[82:85], v[26:33], v[200:207], v[82:85], v1, v1 op_sel_hi:[0,0,0]
	v_mfma_scale_f32_16x16x128_f8f6f4 v[74:77], v[18:25], v[208:215], v[74:77], v1, v1 op_sel_hi:[0,0,0]
	v_mfma_scale_f32_16x16x128_f8f6f4 v[66:69], v[26:33], v[208:215], v[66:69], v1, v1 op_sel_hi:[0,0,0]
	v_mfma_scale_f32_16x16x128_f8f6f4 v[58:61], v[18:25], v[216:223], v[58:61], v1, v1 op_sel_hi:[0,0,0]
	v_mfma_scale_f32_16x16x128_f8f6f4 v[50:53], v[26:33], v[216:223], v[50:53], v1, v1 op_sel_hi:[0,0,0]
	v_mfma_scale_f32_16x16x128_f8f6f4 v[42:45], v[18:25], v[224:231], v[42:45], v1, v1 op_sel_hi:[0,0,0]
	v_mfma_scale_f32_16x16x128_f8f6f4 v[34:37], v[26:33], v[224:231], v[34:37], v1, v1 op_sel_hi:[0,0,0]
	s_add_i32 s0, 0, 0x18000
	v_add_u32_e32 v14, s0, v196
	s_barrier
	ds_read_b128 v[2:5], v14
	ds_read_b128 v[6:9], v14 offset:1024
	ds_read_b128 v[10:13], v14 offset:2048
	ds_read_b128 v[14:17], v14 offset:3072
	s_mov_b32 m0, s47
	ds_read_b128 v[18:21], v169 offset:32768
	ds_read_b128 v[22:25], v169 offset:33792
	ds_read_b128 v[26:29], v169 offset:34816
	ds_read_b128 v[30:33], v169 offset:35840
	ds_read_b128 v[200:203], v169 offset:36864
	ds_read_b128 v[204:207], v169 offset:37888
	ds_read_b128 v[208:211], v169 offset:38912
	ds_read_b128 v[212:215], v169 offset:39936
	global_load_lds_dwordx4 v175, s[36:37]
	s_mov_b32 m0, s48
	s_nop 0
	global_load_lds_dwordx4 v173, s[36:37]
	s_waitcnt lgkmcnt(8)
	s_waitcnt vmcnt(10)
	s_barrier
	s_waitcnt lgkmcnt(0)
	s_waitcnt lgkmcnt(0)
	v_mfma_scale_f32_16x16x128_f8f6f4 v[158:161], v[2:9], v[18:25], v[158:161], v1, v1 op_sel_hi:[0,0,0]
	v_mfma_scale_f32_16x16x128_f8f6f4 v[150:153], v[10:17], v[18:25], v[150:153], v1, v1 op_sel_hi:[0,0,0]
	v_mfma_scale_f32_16x16x128_f8f6f4 v[142:145], v[2:9], v[26:33], v[142:145], v1, v1 op_sel_hi:[0,0,0]
	v_mfma_scale_f32_16x16x128_f8f6f4 v[134:137], v[10:17], v[26:33], v[134:137], v1, v1 op_sel_hi:[0,0,0]
	v_mfma_scale_f32_16x16x128_f8f6f4 v[126:129], v[2:9], v[200:207], v[126:129], v1, v1 op_sel_hi:[0,0,0]
	v_mfma_scale_f32_16x16x128_f8f6f4 v[118:121], v[10:17], v[200:207], v[118:121], v1, v1 op_sel_hi:[0,0,0]
	v_mfma_scale_f32_16x16x128_f8f6f4 v[110:113], v[2:9], v[208:215], v[110:113], v1, v1 op_sel_hi:[0,0,0]
	v_mfma_scale_f32_16x16x128_f8f6f4 v[102:105], v[10:17], v[208:215], v[102:105], v1, v1 op_sel_hi:[0,0,0]
	s_barrier
	s_add_i32 s34, 0, 0x1c000
	s_add_i32 s0, s0, s43
	v_add_u32_e32 v162, s34, v196
	v_lshl_add_u64 v[180:181], v[180:181], 0, s[20:21]
	s_mov_b32 m0, s0
	ds_read_b128 v[216:219], v162
	ds_read_b128 v[220:223], v162 offset:1024
	ds_read_b128 v[224:227], v162 offset:2048
	ds_read_b128 v[228:231], v162 offset:3072
	global_load_lds_dwordx4 v[180:181], off
	v_lshl_add_u64 v[180:181], v[182:183], 0, s[20:21]
	s_add_i32 m0, s0, 0x2000
	s_nop 0
	global_load_lds_dwordx4 v[180:181], off
	s_waitcnt vmcnt(10)
	s_barrier
	s_waitcnt lgkmcnt(0)
	s_waitcnt lgkmcnt(0)
	v_mfma_scale_f32_16x16x128_f8f6f4 v[154:157], v[216:223], v[18:25], v[154:157], v1, v1 op_sel_hi:[0,0,0]
	v_mfma_scale_f32_16x16x128_f8f6f4 v[146:149], v[224:231], v[18:25], v[146:149], v1, v1 op_sel_hi:[0,0,0]
	v_mfma_scale_f32_16x16x128_f8f6f4 v[138:141], v[216:223], v[26:33], v[138:141], v1, v1 op_sel_hi:[0,0,0]
	v_mfma_scale_f32_16x16x128_f8f6f4 v[130:133], v[224:231], v[26:33], v[130:133], v1, v1 op_sel_hi:[0,0,0]
	v_mfma_scale_f32_16x16x128_f8f6f4 v[122:125], v[216:223], v[200:207], v[122:125], v1, v1 op_sel_hi:[0,0,0]
	v_mfma_scale_f32_16x16x128_f8f6f4 v[114:117], v[224:231], v[200:207], v[114:117], v1, v1 op_sel_hi:[0,0,0]
	v_mfma_scale_f32_16x16x128_f8f6f4 v[106:109], v[216:223], v[208:215], v[106:109], v1, v1 op_sel_hi:[0,0,0]
	v_mfma_scale_f32_16x16x128_f8f6f4 v[98:101], v[224:231], v[208:215], v[98:101], v1, v1 op_sel_hi:[0,0,0]
	s_mov_b32 m0, s51
	v_lshl_add_u64 v[180:181], v[186:187], 0, s[20:21]
	s_barrier
	ds_read_b128 v[18:21], v169 offset:49152
	ds_read_b128 v[22:25], v169 offset:50176
	ds_read_b128 v[26:29], v169 offset:51200
	ds_read_b128 v[30:33], v169 offset:52224
	ds_read_b128 v[200:203], v169 offset:53248
	ds_read_b128 v[204:207], v169 offset:54272
	ds_read_b128 v[208:211], v169 offset:55296
	ds_read_b128 v[212:215], v169 offset:56320
	global_load_lds_dwordx4 v[180:181], off
	v_lshl_add_u64 v[180:181], v[184:185], 0, s[20:21]
	s_mov_b32 m0, s52
	s_nop 0
	global_load_lds_dwordx4 v[180:181], off
	s_waitcnt vmcnt(10)
	s_barrier
	s_waitcnt lgkmcnt(0)
	s_waitcnt lgkmcnt(0)
	v_mfma_scale_f32_16x16x128_f8f6f4 v[94:97], v[2:9], v[18:25], v[94:97], v1, v1 op_sel_hi:[0,0,0]
	v_mfma_scale_f32_16x16x128_f8f6f4 v[86:89], v[10:17], v[18:25], v[86:89], v1, v1 op_sel_hi:[0,0,0]
	v_mfma_scale_f32_16x16x128_f8f6f4 v[78:81], v[2:9], v[26:33], v[78:81], v1, v1 op_sel_hi:[0,0,0]
	v_mfma_scale_f32_16x16x128_f8f6f4 v[70:73], v[10:17], v[26:33], v[70:73], v1, v1 op_sel_hi:[0,0,0]
	v_mfma_scale_f32_16x16x128_f8f6f4 v[62:65], v[2:9], v[200:207], v[62:65], v1, v1 op_sel_hi:[0,0,0]
	v_mfma_scale_f32_16x16x128_f8f6f4 v[54:57], v[10:17], v[200:207], v[54:57], v1, v1 op_sel_hi:[0,0,0]
	v_mfma_scale_f32_16x16x128_f8f6f4 v[46:49], v[2:9], v[208:215], v[46:49], v1, v1 op_sel_hi:[0,0,0]
	v_mfma_scale_f32_16x16x128_f8f6f4 v[38:41], v[10:17], v[208:215], v[38:41], v1, v1 op_sel_hi:[0,0,0]
	s_barrier
	s_add_u32 s0, s30, 0x20080
	s_addc_u32 s1, s31, 0
	s_add_i32 s30, s34, s43
	v_lshl_add_u64 v[2:3], s[0:1], 0, v[164:165]
	s_mov_b32 m0, s30
	s_nop 0
	global_load_lds_dwordx4 v[2:3], off
	v_lshl_add_u64 v[2:3], s[0:1], 0, v[166:167]
	s_add_i32 m0, s30, 0x2000
	s_nop 0
	global_load_lds_dwordx4 v[2:3], off
	s_waitcnt vmcnt(10)
	s_barrier
	v_mfma_scale_f32_16x16x128_f8f6f4 v[90:93], v[216:223], v[18:25], v[90:93], v1, v1 op_sel_hi:[0,0,0]
	v_mfma_scale_f32_16x16x128_f8f6f4 v[82:85], v[224:231], v[18:25], v[82:85], v1, v1 op_sel_hi:[0,0,0]
	v_mfma_scale_f32_16x16x128_f8f6f4 v[74:77], v[216:223], v[26:33], v[74:77], v1, v1 op_sel_hi:[0,0,0]
	v_mfma_scale_f32_16x16x128_f8f6f4 v[66:69], v[224:231], v[26:33], v[66:69], v1, v1 op_sel_hi:[0,0,0]
	v_mfma_scale_f32_16x16x128_f8f6f4 v[58:61], v[216:223], v[200:207], v[58:61], v1, v1 op_sel_hi:[0,0,0]
	v_mfma_scale_f32_16x16x128_f8f6f4 v[50:53], v[224:231], v[200:207], v[50:53], v1, v1 op_sel_hi:[0,0,0]
	v_mfma_scale_f32_16x16x128_f8f6f4 v[42:45], v[216:223], v[208:215], v[42:45], v1, v1 op_sel_hi:[0,0,0]
	v_mfma_scale_f32_16x16x128_f8f6f4 v[34:37], v[224:231], v[208:215], v[34:37], v1, v1 op_sel_hi:[0,0,0]
	s_add_i32 s56, s56, 2
	s_cmp_gt_u32 s56, 5
	s_mov_b64 s[34:35], s[10:11]
	s_barrier
	s_cbranch_scc0 .LBB0_2749
	v_mul_f32_e32 v5, 0x3c800000, v158
	v_mul_f32_e32 v6, 0xbfb8aa3b, v5
	v_exp_f32_e32 v6, v6
	s_ashr_i32 s29, s28, 31
	s_ashr_i32 s27, s26, 31
	s_lshl_b64 s[10:11], s[28:29], 18
	v_add_f32_e32 v6, 1.0, v6
	v_rcp_f32_e32 v6, v6
	s_lshl_b64 s[26:27], s[26:27], 15
	v_mov_b32_e32 v3, v194
	s_add_u32 s0, s8, s10
	v_mul_f32_e32 v5, v5, v6
	v_mul_f32_e32 v6, 0x3c800000, v159
	v_mul_f32_e32 v7, 0xbfb8aa3b, v6
	v_exp_f32_e32 v7, v7
	v_mul_f32_e32 v5, v5, v154
	v_mul_f32_e32 v5, 0x3e000000, v5
	v_med3_f32 v5, v5, s40, v189
	v_add_f32_e32 v7, 1.0, v7
	v_rcp_f32_e32 v7, v7
	s_nop 15
	s_nop 15
	v_mov_b32_e32 v2, v195
	v_mul_f32_e32 v6, v6, v7
	v_mul_f32_e32 v7, 0x3c800000, v160
	v_mul_f32_e32 v8, 0xbfb8aa3b, v7
	v_exp_f32_e32 v8, v8
	v_mul_f32_e32 v6, v6, v155
	v_mul_f32_e32 v6, 0x3e000000, v6
	v_add_u32_e32 v4, s49, v3
	v_add_f32_e32 v8, 1.0, v8
	v_rcp_f32_e32 v8, v8
	s_addc_u32 s1, s9, s11
	s_add_u32 s10, s0, s26
	v_mul_f32_e32 v7, v7, v8
	v_mul_f32_e32 v8, 0x3c800000, v161
	v_mul_f32_e32 v9, 0xbfb8aa3b, v8
	v_exp_f32_e32 v9, v9
	v_mul_f32_e32 v7, v7, v156
	v_mul_f32_e32 v7, 0x3e000000, v7
	v_lshl_add_u32 v2, v2, 3, s50
	v_add_f32_e32 v9, 1.0, v9
	v_rcp_f32_e32 v9, v9
	s_addc_u32 s11, s1, s27
	v_ashrrev_i32_e32 v3, 31, v2
	s_and_b64 vcc, exec, s[6:7]
	v_mul_f32_e32 v8, v8, v9
	v_mul_f32_e32 v9, 0x3c800000, v150
	v_mul_f32_e32 v10, 0xbfb8aa3b, v9
	v_exp_f32_e32 v10, v10
	v_mul_f32_e32 v8, v8, v157
	v_mul_f32_e32 v8, 0x3e000000, v8
	v_mov_b32_e32 v174, v199
	v_add_f32_e32 v10, 1.0, v10
	v_rcp_f32_e32 v10, v10
	v_mov_b32_e32 v172, v198
	v_mov_b32_e32 v170, v197
	v_mov_b32_e32 v168, v171
	v_mul_f32_e32 v9, v9, v10
	v_mul_f32_e32 v10, 0x3c800000, v151
	v_mul_f32_e32 v11, 0xbfb8aa3b, v10
	v_exp_f32_e32 v11, v11
	v_mul_f32_e32 v9, v9, v146
	v_mul_f32_e32 v9, 0x3e000000, v9
	s_mov_b32 s26, s24
	v_add_f32_e32 v11, 1.0, v11
	v_rcp_f32_e32 v11, v11
	s_mov_b32 s28, s54
	s_mov_b64 s[30:31], s[12:13]
	v_mul_f32_e32 v10, v10, v11
	v_mul_f32_e32 v11, 0x3c800000, v152
	v_mul_f32_e32 v12, 0xbfb8aa3b, v11
	v_exp_f32_e32 v12, v12
	v_mul_f32_e32 v10, v10, v147
	v_mul_f32_e32 v10, 0x3e000000, v10
	v_add_f32_e32 v12, 1.0, v12
	v_rcp_f32_e32 v12, v12
	s_nop 0
	v_mul_f32_e32 v11, v11, v12
	v_mul_f32_e32 v12, 0x3c800000, v153
	v_mul_f32_e32 v13, 0xbfb8aa3b, v12
	v_exp_f32_e32 v13, v13
	v_mul_f32_e32 v11, v11, v148
	v_mul_f32_e32 v11, 0x3e000000, v11
	v_add_f32_e32 v13, 1.0, v13
	v_rcp_f32_e32 v13, v13
	s_nop 0
	v_mul_f32_e32 v12, v12, v13
	v_med3_f32 v13, v6, s40, v189
	v_mov_b32_e32 v6, v163
	v_cvt_pk_fp8_f32 v6, v5, v13
	v_med3_f32 v5, v7, s40, v189
	v_med3_f32 v7, v8, s40, v189
	v_med3_f32 v8, v10, s40, v189
	v_cvt_pk_fp8_f32 v6, v5, v7 op_sel:[0,0,1]
	v_med3_f32 v5, v9, s40, v189
	v_mov_b32_e32 v7, v163
	v_cvt_pk_fp8_f32 v7, v5, v8
	v_mul_f32_e32 v12, v12, v149
	v_mul_f32_e32 v12, 0x3e000000, v12
	v_med3_f32 v5, v11, s40, v189
	v_med3_f32 v8, v12, s40, v189
	v_cvt_pk_fp8_f32 v7, v5, v8 op_sel:[0,0,1]
	v_ashrrev_i32_e32 v5, 31, v4
	v_lshlrev_b64 v[8:9], 7, v[4:5]
	v_lshl_add_u64 v[8:9], s[10:11], 0, v[8:9]
	v_lshl_add_u64 v[8:9], v[8:9], 0, v[2:3]
	v_mul_f32_e32 v5, 0x3c800000, v142
	global_store_dwordx2 v[8:9], v[6:7], off
	v_mul_f32_e32 v6, 0xbfb8aa3b, v5
	v_exp_f32_e32 v6, v6
	s_nop 0
	v_add_f32_e32 v6, 1.0, v6
	v_rcp_f32_e32 v6, v6
	s_nop 0
	v_mul_f32_e32 v5, v5, v6
	v_mul_f32_e32 v6, 0x3c800000, v143
	v_mul_f32_e32 v7, 0xbfb8aa3b, v6
	v_exp_f32_e32 v7, v7
	v_mul_f32_e32 v5, v5, v138
	v_mul_f32_e32 v5, 0x3e000000, v5
	v_med3_f32 v5, v5, s40, v189
	v_add_f32_e32 v7, 1.0, v7
	v_rcp_f32_e32 v7, v7
	s_nop 0
	v_mul_f32_e32 v6, v6, v7
	v_mul_f32_e32 v6, v6, v139
	v_mul_f32_e32 v7, 0x3e000000, v6
	v_mul_f32_e32 v6, 0x3c800000, v144
	v_mul_f32_e32 v8, 0xbfb8aa3b, v6
	v_exp_f32_e32 v8, v8
	v_med3_f32 v7, v7, s40, v189
	v_add_f32_e32 v8, 1.0, v8
	v_rcp_f32_e32 v8, v8
	s_nop 0
	v_mul_f32_e32 v6, v6, v8
	v_mul_f32_e32 v6, v6, v140
	v_mul_f32_e32 v9, 0x3e000000, v6
	v_mul_f32_e32 v6, 0x3c800000, v145
	v_mul_f32_e32 v8, 0xbfb8aa3b, v6
	v_exp_f32_e32 v8, v8
	s_nop 0
	v_add_f32_e32 v8, 1.0, v8
	v_rcp_f32_e32 v8, v8
	s_nop 0
	v_mul_f32_e32 v6, v6, v8
	v_mul_f32_e32 v6, v6, v141
	v_mul_f32_e32 v10, 0x3e000000, v6
	v_mul_f32_e32 v6, 0x3c800000, v134
	v_mul_f32_e32 v8, 0xbfb8aa3b, v6
	v_exp_f32_e32 v8, v8
	s_nop 0
	v_add_f32_e32 v8, 1.0, v8
	v_rcp_f32_e32 v8, v8
	s_nop 0
	v_mul_f32_e32 v6, v6, v8
	v_mul_f32_e32 v6, v6, v130
	v_mul_f32_e32 v11, 0x3e000000, v6
	v_mul_f32_e32 v6, 0x3c800000, v135
	v_mul_f32_e32 v8, 0xbfb8aa3b, v6
	v_exp_f32_e32 v8, v8
	s_nop 0
	v_add_f32_e32 v8, 1.0, v8
	v_rcp_f32_e32 v8, v8
	s_nop 0
	v_mul_f32_e32 v6, v6, v8
	v_mul_f32_e32 v6, v6, v131
	v_mul_f32_e32 v12, 0x3e000000, v6
	v_mul_f32_e32 v6, 0x3c800000, v136
	v_mul_f32_e32 v8, 0xbfb8aa3b, v6
	v_exp_f32_e32 v8, v8
	s_nop 0
	v_add_f32_e32 v8, 1.0, v8
	v_rcp_f32_e32 v8, v8
	s_nop 0
	v_mul_f32_e32 v6, v6, v8
	v_mul_f32_e32 v6, v6, v132
	v_mul_f32_e32 v13, 0x3e000000, v6
	v_mul_f32_e32 v6, 0x3c800000, v137
	v_mul_f32_e32 v8, 0xbfb8aa3b, v6
	v_exp_f32_e32 v8, v8
	s_nop 0
	v_add_f32_e32 v8, 1.0, v8
	v_rcp_f32_e32 v8, v8
	s_nop 0
	v_mul_f32_e32 v6, v6, v8
	v_mov_b32_e32 v8, v163
	v_cvt_pk_fp8_f32 v8, v5, v7
	v_med3_f32 v5, v9, s40, v189
	v_med3_f32 v7, v10, s40, v189
	v_mov_b32_e32 v9, v163
	v_cvt_pk_fp8_f32 v8, v5, v7 op_sel:[0,0,1]
	v_med3_f32 v5, v11, s40, v189
	v_med3_f32 v7, v12, s40, v189
	v_cvt_pk_fp8_f32 v9, v5, v7
	v_mul_f32_e32 v6, v6, v133
	v_mul_f32_e32 v14, 0x3e000000, v6
	v_add_u32_e32 v6, 16, v4
	v_med3_f32 v5, v13, s40, v189
	v_med3_f32 v7, v14, s40, v189
	v_cvt_pk_fp8_f32 v9, v5, v7 op_sel:[0,0,1]
	v_ashrrev_i32_e32 v7, 31, v6
	v_lshlrev_b64 v[6:7], 7, v[6:7]
	v_lshl_add_u64 v[6:7], s[10:11], 0, v[6:7]
	v_lshl_add_u64 v[6:7], v[6:7], 0, v[2:3]
	v_mul_f32_e32 v5, 0x3c800000, v126
	global_store_dwordx2 v[6:7], v[8:9], off
	v_mul_f32_e32 v6, 0xbfb8aa3b, v5
	v_exp_f32_e32 v6, v6
	s_nop 0
	v_add_f32_e32 v6, 1.0, v6
	v_rcp_f32_e32 v6, v6
	s_nop 0
	v_mul_f32_e32 v5, v5, v6
	v_mul_f32_e32 v6, 0x3c800000, v127
	v_mul_f32_e32 v7, 0xbfb8aa3b, v6
	v_exp_f32_e32 v7, v7
	v_mul_f32_e32 v5, v5, v122
	v_mul_f32_e32 v5, 0x3e000000, v5
	v_med3_f32 v5, v5, s40, v189
	v_add_f32_e32 v7, 1.0, v7
	v_rcp_f32_e32 v7, v7
	s_nop 0
	v_mul_f32_e32 v6, v6, v7
	v_mul_f32_e32 v6, v6, v123
	v_mul_f32_e32 v7, 0x3e000000, v6
	v_mul_f32_e32 v6, 0x3c800000, v128
	v_mul_f32_e32 v8, 0xbfb8aa3b, v6
	v_exp_f32_e32 v8, v8
	v_med3_f32 v7, v7, s40, v189
	v_add_f32_e32 v8, 1.0, v8
	v_rcp_f32_e32 v8, v8
	s_nop 0
	v_mul_f32_e32 v6, v6, v8
	v_mul_f32_e32 v6, v6, v124
	v_mul_f32_e32 v9, 0x3e000000, v6
	v_mul_f32_e32 v6, 0x3c800000, v129
	v_mul_f32_e32 v8, 0xbfb8aa3b, v6
	v_exp_f32_e32 v8, v8
	s_nop 0
	v_add_f32_e32 v8, 1.0, v8
	v_rcp_f32_e32 v8, v8
	s_nop 0
	v_mul_f32_e32 v6, v6, v8
	v_mul_f32_e32 v6, v6, v125
	v_mul_f32_e32 v10, 0x3e000000, v6
	v_mul_f32_e32 v6, 0x3c800000, v118
	v_mul_f32_e32 v8, 0xbfb8aa3b, v6
	v_exp_f32_e32 v8, v8
	s_nop 0
	v_add_f32_e32 v8, 1.0, v8
	v_rcp_f32_e32 v8, v8
	s_nop 0
	v_mul_f32_e32 v6, v6, v8
	v_mul_f32_e32 v6, v6, v114
	v_mul_f32_e32 v11, 0x3e000000, v6
	v_mul_f32_e32 v6, 0x3c800000, v119
	v_mul_f32_e32 v8, 0xbfb8aa3b, v6
	v_exp_f32_e32 v8, v8
	s_nop 0
	v_add_f32_e32 v8, 1.0, v8
	v_rcp_f32_e32 v8, v8
	s_nop 0
	v_mul_f32_e32 v6, v6, v8
	v_mul_f32_e32 v6, v6, v115
	v_mul_f32_e32 v12, 0x3e000000, v6
	v_mul_f32_e32 v6, 0x3c800000, v120
	v_mul_f32_e32 v8, 0xbfb8aa3b, v6
	v_exp_f32_e32 v8, v8
	s_nop 0
	v_add_f32_e32 v8, 1.0, v8
	v_rcp_f32_e32 v8, v8
	s_nop 0
	v_mul_f32_e32 v6, v6, v8
	v_mul_f32_e32 v6, v6, v116
	v_mul_f32_e32 v13, 0x3e000000, v6
	v_mul_f32_e32 v6, 0x3c800000, v121
	v_mul_f32_e32 v8, 0xbfb8aa3b, v6
	v_exp_f32_e32 v8, v8
	s_nop 0
	v_add_f32_e32 v8, 1.0, v8
	v_rcp_f32_e32 v8, v8
	s_nop 0
	v_mul_f32_e32 v6, v6, v8
	v_mov_b32_e32 v8, v163
	v_cvt_pk_fp8_f32 v8, v5, v7
	v_med3_f32 v5, v9, s40, v189
	v_med3_f32 v7, v10, s40, v189
	v_mov_b32_e32 v9, v163
	v_cvt_pk_fp8_f32 v8, v5, v7 op_sel:[0,0,1]
	v_med3_f32 v5, v11, s40, v189
	v_med3_f32 v7, v12, s40, v189
	v_cvt_pk_fp8_f32 v9, v5, v7
	v_mul_f32_e32 v6, v6, v117
	v_mul_f32_e32 v14, 0x3e000000, v6
	v_add_u32_e32 v6, 32, v4
	v_med3_f32 v5, v13, s40, v189
	v_med3_f32 v7, v14, s40, v189
	v_cvt_pk_fp8_f32 v9, v5, v7 op_sel:[0,0,1]
	v_ashrrev_i32_e32 v7, 31, v6
	v_lshlrev_b64 v[6:7], 7, v[6:7]
	v_lshl_add_u64 v[6:7], s[10:11], 0, v[6:7]
	v_lshl_add_u64 v[6:7], v[6:7], 0, v[2:3]
	v_mul_f32_e32 v5, 0x3c800000, v110
	global_store_dwordx2 v[6:7], v[8:9], off
	v_mul_f32_e32 v6, 0xbfb8aa3b, v5
	v_exp_f32_e32 v6, v6
	s_nop 0
	v_add_f32_e32 v6, 1.0, v6
	v_rcp_f32_e32 v6, v6
	s_nop 0
	v_mul_f32_e32 v5, v5, v6
	v_mul_f32_e32 v6, 0x3c800000, v111
	v_mul_f32_e32 v7, 0xbfb8aa3b, v6
	v_exp_f32_e32 v7, v7
	v_mul_f32_e32 v5, v5, v106
	v_mul_f32_e32 v5, 0x3e000000, v5
	v_med3_f32 v5, v5, s40, v189
	v_add_f32_e32 v7, 1.0, v7
	v_rcp_f32_e32 v7, v7
	s_nop 0
	v_mul_f32_e32 v6, v6, v7
	v_mul_f32_e32 v6, v6, v107
	v_mul_f32_e32 v7, 0x3e000000, v6
	v_mul_f32_e32 v6, 0x3c800000, v112
	v_mul_f32_e32 v8, 0xbfb8aa3b, v6
	v_exp_f32_e32 v8, v8
	v_med3_f32 v7, v7, s40, v189
	v_add_f32_e32 v8, 1.0, v8
	v_rcp_f32_e32 v8, v8
	s_nop 0
	v_mul_f32_e32 v6, v6, v8
	v_mul_f32_e32 v6, v6, v108
	v_mul_f32_e32 v9, 0x3e000000, v6
	v_mul_f32_e32 v6, 0x3c800000, v113
	v_mul_f32_e32 v8, 0xbfb8aa3b, v6
	v_exp_f32_e32 v8, v8
	s_nop 0
	v_add_f32_e32 v8, 1.0, v8
	v_rcp_f32_e32 v8, v8
	s_nop 0
	v_mul_f32_e32 v6, v6, v8
	v_mul_f32_e32 v6, v6, v109
	v_mul_f32_e32 v10, 0x3e000000, v6
	v_mul_f32_e32 v6, 0x3c800000, v102
	v_mul_f32_e32 v8, 0xbfb8aa3b, v6
	v_exp_f32_e32 v8, v8
	s_nop 0
	v_add_f32_e32 v8, 1.0, v8
	v_rcp_f32_e32 v8, v8
	s_nop 0
	v_mul_f32_e32 v6, v6, v8
	v_mul_f32_e32 v6, v6, v98
	v_mul_f32_e32 v11, 0x3e000000, v6
	v_mul_f32_e32 v6, 0x3c800000, v103
	v_mul_f32_e32 v8, 0xbfb8aa3b, v6
	v_exp_f32_e32 v8, v8
	s_nop 0
	v_add_f32_e32 v8, 1.0, v8
	v_rcp_f32_e32 v8, v8
	s_nop 0
	v_mul_f32_e32 v6, v6, v8
	v_mul_f32_e32 v6, v6, v99
	v_mul_f32_e32 v12, 0x3e000000, v6
	v_mul_f32_e32 v6, 0x3c800000, v104
	v_mul_f32_e32 v8, 0xbfb8aa3b, v6
	v_exp_f32_e32 v8, v8
	s_nop 0
	v_add_f32_e32 v8, 1.0, v8
	v_rcp_f32_e32 v8, v8
	s_nop 0
	v_mul_f32_e32 v6, v6, v8
	v_mul_f32_e32 v6, v6, v100
	v_mul_f32_e32 v13, 0x3e000000, v6
	v_mul_f32_e32 v6, 0x3c800000, v105
	v_mul_f32_e32 v8, 0xbfb8aa3b, v6
	v_exp_f32_e32 v8, v8
	s_nop 0
	v_add_f32_e32 v8, 1.0, v8
	v_rcp_f32_e32 v8, v8
	s_nop 0
	v_mul_f32_e32 v6, v6, v8
	v_mov_b32_e32 v8, v163
	v_cvt_pk_fp8_f32 v8, v5, v7
	v_med3_f32 v5, v9, s40, v189
	v_med3_f32 v7, v10, s40, v189
	v_mov_b32_e32 v9, v163
	v_cvt_pk_fp8_f32 v8, v5, v7 op_sel:[0,0,1]
	v_med3_f32 v5, v11, s40, v189
	v_med3_f32 v7, v12, s40, v189
	v_cvt_pk_fp8_f32 v9, v5, v7
	v_mul_f32_e32 v6, v6, v101
	v_mul_f32_e32 v14, 0x3e000000, v6
	v_add_u32_e32 v6, 48, v4
	v_med3_f32 v5, v13, s40, v189
	v_med3_f32 v7, v14, s40, v189
	v_cvt_pk_fp8_f32 v9, v5, v7 op_sel:[0,0,1]
	v_ashrrev_i32_e32 v7, 31, v6
	v_lshlrev_b64 v[6:7], 7, v[6:7]
	v_lshl_add_u64 v[6:7], s[10:11], 0, v[6:7]
	v_lshl_add_u64 v[6:7], v[6:7], 0, v[2:3]
	v_mul_f32_e32 v5, 0x3c800000, v94
	global_store_dwordx2 v[6:7], v[8:9], off
	v_mul_f32_e32 v7, 0xbfb8aa3b, v5
	v_exp_f32_e32 v7, v7
	v_add_u32_e32 v6, 0x80, v4
	v_add_f32_e32 v7, 1.0, v7
	v_rcp_f32_e32 v7, v7
	s_nop 0
	v_mul_f32_e32 v5, v5, v7
	v_mul_f32_e32 v7, 0x3c800000, v95
	v_mul_f32_e32 v8, 0xbfb8aa3b, v7
	v_exp_f32_e32 v8, v8
	v_mul_f32_e32 v5, v5, v90
	v_mul_f32_e32 v5, 0x3e000000, v5
	v_med3_f32 v5, v5, s40, v189
	v_add_f32_e32 v8, 1.0, v8
	v_rcp_f32_e32 v8, v8
	s_nop 0
	v_mul_f32_e32 v7, v7, v8
	v_mul_f32_e32 v8, 0x3c800000, v96
	v_mul_f32_e32 v9, 0xbfb8aa3b, v8
	v_exp_f32_e32 v9, v9
	v_mul_f32_e32 v7, v7, v91
	v_mul_f32_e32 v7, 0x3e000000, v7
	v_med3_f32 v7, v7, s40, v189
	v_add_f32_e32 v9, 1.0, v9
	v_rcp_f32_e32 v9, v9
	s_nop 0
	v_mul_f32_e32 v8, v8, v9
	v_mul_f32_e32 v8, v8, v92
	v_mul_f32_e32 v9, 0x3e000000, v8
	v_mul_f32_e32 v8, 0x3c800000, v97
	v_mul_f32_e32 v10, 0xbfb8aa3b, v8
	v_exp_f32_e32 v10, v10
	s_nop 0
	v_add_f32_e32 v10, 1.0, v10
	v_rcp_f32_e32 v10, v10
	s_nop 0
	v_mul_f32_e32 v8, v8, v10
	v_mul_f32_e32 v8, v8, v93
	v_mul_f32_e32 v10, 0x3e000000, v8
	v_mul_f32_e32 v8, 0x3c800000, v86
	v_mul_f32_e32 v11, 0xbfb8aa3b, v8
	v_exp_f32_e32 v11, v11
	s_nop 0
	v_add_f32_e32 v11, 1.0, v11
	v_rcp_f32_e32 v11, v11
	s_nop 0
	v_mul_f32_e32 v8, v8, v11
	v_mul_f32_e32 v8, v8, v82
	v_mul_f32_e32 v11, 0x3e000000, v8
	v_mul_f32_e32 v8, 0x3c800000, v87
	v_mul_f32_e32 v12, 0xbfb8aa3b, v8
	v_exp_f32_e32 v12, v12
	s_nop 0
	v_add_f32_e32 v12, 1.0, v12
	v_rcp_f32_e32 v12, v12
	s_nop 0
	v_mul_f32_e32 v8, v8, v12
	v_mul_f32_e32 v8, v8, v83
	v_mul_f32_e32 v12, 0x3e000000, v8
	v_mul_f32_e32 v8, 0x3c800000, v88
	v_mul_f32_e32 v13, 0xbfb8aa3b, v8
	v_exp_f32_e32 v13, v13
	s_nop 0
	v_add_f32_e32 v13, 1.0, v13
	v_rcp_f32_e32 v13, v13
	s_nop 0
	v_mul_f32_e32 v8, v8, v13
	v_mul_f32_e32 v8, v8, v84
	v_mul_f32_e32 v13, 0x3e000000, v8
	v_mul_f32_e32 v8, 0x3c800000, v89
	v_mul_f32_e32 v14, 0xbfb8aa3b, v8
	v_exp_f32_e32 v14, v14
	s_nop 0
	v_add_f32_e32 v14, 1.0, v14
	v_rcp_f32_e32 v14, v14
	s_nop 0
	v_mul_f32_e32 v8, v8, v14
	v_mul_f32_e32 v8, v8, v85
	v_mul_f32_e32 v14, 0x3e000000, v8
	v_mov_b32_e32 v8, v163
	v_cvt_pk_fp8_f32 v8, v5, v7
	v_med3_f32 v5, v9, s40, v189
	v_med3_f32 v7, v10, s40, v189
	v_mov_b32_e32 v9, v163
	v_cvt_pk_fp8_f32 v8, v5, v7 op_sel:[0,0,1]
	v_med3_f32 v5, v11, s40, v189
	v_med3_f32 v7, v12, s40, v189
	v_cvt_pk_fp8_f32 v9, v5, v7
	v_med3_f32 v5, v13, s40, v189
	v_med3_f32 v7, v14, s40, v189
	v_cvt_pk_fp8_f32 v9, v5, v7 op_sel:[0,0,1]
	v_ashrrev_i32_e32 v7, 31, v6
	v_lshlrev_b64 v[6:7], 7, v[6:7]
	v_lshl_add_u64 v[6:7], s[10:11], 0, v[6:7]
	v_lshl_add_u64 v[6:7], v[6:7], 0, v[2:3]
	v_mul_f32_e32 v5, 0x3c800000, v78
	global_store_dwordx2 v[6:7], v[8:9], off
	v_mul_f32_e32 v6, 0xbfb8aa3b, v5
	v_exp_f32_e32 v6, v6
	s_nop 0
	v_add_f32_e32 v6, 1.0, v6
	v_rcp_f32_e32 v6, v6
	s_nop 0
	v_mul_f32_e32 v5, v5, v6
	v_mul_f32_e32 v6, 0x3c800000, v79
	v_mul_f32_e32 v7, 0xbfb8aa3b, v6
	v_exp_f32_e32 v7, v7
	v_mul_f32_e32 v5, v5, v74
	v_mul_f32_e32 v5, 0x3e000000, v5
	v_med3_f32 v5, v5, s40, v189
	v_add_f32_e32 v7, 1.0, v7
	v_rcp_f32_e32 v7, v7
	s_nop 0
	v_mul_f32_e32 v6, v6, v7
	v_mul_f32_e32 v6, v6, v75
	v_mul_f32_e32 v7, 0x3e000000, v6
	v_mul_f32_e32 v6, 0x3c800000, v80
	v_mul_f32_e32 v8, 0xbfb8aa3b, v6
	v_exp_f32_e32 v8, v8
	v_med3_f32 v7, v7, s40, v189
	v_add_f32_e32 v8, 1.0, v8
	v_rcp_f32_e32 v8, v8
	s_nop 0
	v_mul_f32_e32 v6, v6, v8
	v_mul_f32_e32 v6, v6, v76
	v_mul_f32_e32 v9, 0x3e000000, v6
	v_mul_f32_e32 v6, 0x3c800000, v81
	v_mul_f32_e32 v8, 0xbfb8aa3b, v6
	v_exp_f32_e32 v8, v8
	s_nop 0
	v_add_f32_e32 v8, 1.0, v8
	v_rcp_f32_e32 v8, v8
	s_nop 0
	v_mul_f32_e32 v6, v6, v8
	v_mul_f32_e32 v6, v6, v77
	v_mul_f32_e32 v10, 0x3e000000, v6
	v_mul_f32_e32 v6, 0x3c800000, v70
	v_mul_f32_e32 v8, 0xbfb8aa3b, v6
	v_exp_f32_e32 v8, v8
	s_nop 0
	v_add_f32_e32 v8, 1.0, v8
	v_rcp_f32_e32 v8, v8
	s_nop 0
	v_mul_f32_e32 v6, v6, v8
	v_mul_f32_e32 v6, v6, v66
	v_mul_f32_e32 v11, 0x3e000000, v6
	v_mul_f32_e32 v6, 0x3c800000, v71
	v_mul_f32_e32 v8, 0xbfb8aa3b, v6
	v_exp_f32_e32 v8, v8
	s_nop 0
	v_add_f32_e32 v8, 1.0, v8
	v_rcp_f32_e32 v8, v8
	s_nop 0
	v_mul_f32_e32 v6, v6, v8
	v_mul_f32_e32 v6, v6, v67
	v_mul_f32_e32 v12, 0x3e000000, v6
	v_mul_f32_e32 v6, 0x3c800000, v72
	v_mul_f32_e32 v8, 0xbfb8aa3b, v6
	v_exp_f32_e32 v8, v8
	s_nop 0
	v_add_f32_e32 v8, 1.0, v8
	v_rcp_f32_e32 v8, v8
	s_nop 0
	v_mul_f32_e32 v6, v6, v8
	v_mul_f32_e32 v6, v6, v68
	v_mul_f32_e32 v13, 0x3e000000, v6
	v_mul_f32_e32 v6, 0x3c800000, v73
	v_mul_f32_e32 v8, 0xbfb8aa3b, v6
	v_exp_f32_e32 v8, v8
	s_nop 0
	v_add_f32_e32 v8, 1.0, v8
	v_rcp_f32_e32 v8, v8
	s_nop 0
	v_mul_f32_e32 v6, v6, v8
	v_mov_b32_e32 v8, v163
	v_cvt_pk_fp8_f32 v8, v5, v7
	v_med3_f32 v5, v9, s40, v189
	v_med3_f32 v7, v10, s40, v189
	v_mov_b32_e32 v9, v163
	v_cvt_pk_fp8_f32 v8, v5, v7 op_sel:[0,0,1]
	v_med3_f32 v5, v11, s40, v189
	v_med3_f32 v7, v12, s40, v189
	v_cvt_pk_fp8_f32 v9, v5, v7
	v_mul_f32_e32 v6, v6, v69
	v_mul_f32_e32 v14, 0x3e000000, v6
	v_add_u32_e32 v6, 0x90, v4
	v_med3_f32 v5, v13, s40, v189
	v_med3_f32 v7, v14, s40, v189
	v_cvt_pk_fp8_f32 v9, v5, v7 op_sel:[0,0,1]
	v_ashrrev_i32_e32 v7, 31, v6
	v_lshlrev_b64 v[6:7], 7, v[6:7]
	v_lshl_add_u64 v[6:7], s[10:11], 0, v[6:7]
	v_lshl_add_u64 v[6:7], v[6:7], 0, v[2:3]
	v_mul_f32_e32 v5, 0x3c800000, v62
	global_store_dwordx2 v[6:7], v[8:9], off
	v_mul_f32_e32 v6, 0xbfb8aa3b, v5
	v_exp_f32_e32 v6, v6
	s_nop 0
	v_add_f32_e32 v6, 1.0, v6
	v_rcp_f32_e32 v6, v6
	s_nop 0
	v_mul_f32_e32 v5, v5, v6
	v_mul_f32_e32 v6, 0x3c800000, v63
	v_mul_f32_e32 v7, 0xbfb8aa3b, v6
	v_exp_f32_e32 v7, v7
	v_mul_f32_e32 v5, v5, v58
	v_mul_f32_e32 v5, 0x3e000000, v5
	v_med3_f32 v5, v5, s40, v189
	v_add_f32_e32 v7, 1.0, v7
	v_rcp_f32_e32 v7, v7
	s_nop 0
	v_mul_f32_e32 v6, v6, v7
	v_mul_f32_e32 v6, v6, v59
	v_mul_f32_e32 v7, 0x3e000000, v6
	v_mul_f32_e32 v6, 0x3c800000, v64
	v_mul_f32_e32 v8, 0xbfb8aa3b, v6
	v_exp_f32_e32 v8, v8
	v_med3_f32 v7, v7, s40, v189
	v_add_f32_e32 v8, 1.0, v8
	v_rcp_f32_e32 v8, v8
	s_nop 0
	v_mul_f32_e32 v6, v6, v8
	v_mul_f32_e32 v6, v6, v60
	v_mul_f32_e32 v9, 0x3e000000, v6
	v_mul_f32_e32 v6, 0x3c800000, v65
	v_mul_f32_e32 v8, 0xbfb8aa3b, v6
	v_exp_f32_e32 v8, v8
	s_nop 0
	v_add_f32_e32 v8, 1.0, v8
	v_rcp_f32_e32 v8, v8
	s_nop 0
	v_mul_f32_e32 v6, v6, v8
	v_mul_f32_e32 v6, v6, v61
	v_mul_f32_e32 v10, 0x3e000000, v6
	v_mul_f32_e32 v6, 0x3c800000, v54
	v_mul_f32_e32 v8, 0xbfb8aa3b, v6
	v_exp_f32_e32 v8, v8
	s_nop 0
	v_add_f32_e32 v8, 1.0, v8
	v_rcp_f32_e32 v8, v8
	s_nop 0
	v_mul_f32_e32 v6, v6, v8
	v_mul_f32_e32 v6, v6, v50
	v_mul_f32_e32 v11, 0x3e000000, v6
	v_mul_f32_e32 v6, 0x3c800000, v55
	v_mul_f32_e32 v8, 0xbfb8aa3b, v6
	v_exp_f32_e32 v8, v8
	s_nop 0
	v_add_f32_e32 v8, 1.0, v8
	v_rcp_f32_e32 v8, v8
	s_nop 0
	v_mul_f32_e32 v6, v6, v8
	v_mul_f32_e32 v6, v6, v51
	v_mul_f32_e32 v12, 0x3e000000, v6
	v_mul_f32_e32 v6, 0x3c800000, v56
	v_mul_f32_e32 v8, 0xbfb8aa3b, v6
	v_exp_f32_e32 v8, v8
	s_nop 0
	v_add_f32_e32 v8, 1.0, v8
	v_rcp_f32_e32 v8, v8
	s_nop 0
	v_mul_f32_e32 v6, v6, v8
	v_mul_f32_e32 v6, v6, v52
	v_mul_f32_e32 v13, 0x3e000000, v6
	v_mul_f32_e32 v6, 0x3c800000, v57
	v_mul_f32_e32 v8, 0xbfb8aa3b, v6
	v_exp_f32_e32 v8, v8
	s_nop 0
	v_add_f32_e32 v8, 1.0, v8
	v_rcp_f32_e32 v8, v8
	s_nop 0
	v_mul_f32_e32 v6, v6, v8
	v_mov_b32_e32 v8, v163
	v_cvt_pk_fp8_f32 v8, v5, v7
	v_med3_f32 v5, v9, s40, v189
	v_med3_f32 v7, v10, s40, v189
	v_mov_b32_e32 v9, v163
	v_cvt_pk_fp8_f32 v8, v5, v7 op_sel:[0,0,1]
	v_med3_f32 v5, v11, s40, v189
	v_med3_f32 v7, v12, s40, v189
	v_cvt_pk_fp8_f32 v9, v5, v7
	v_mul_f32_e32 v6, v6, v53
	v_mul_f32_e32 v14, 0x3e000000, v6
	v_add_u32_e32 v6, 0xa0, v4
	v_med3_f32 v5, v13, s40, v189
	v_med3_f32 v7, v14, s40, v189
	v_cvt_pk_fp8_f32 v9, v5, v7 op_sel:[0,0,1]
	v_ashrrev_i32_e32 v7, 31, v6
	v_lshlrev_b64 v[6:7], 7, v[6:7]
	v_lshl_add_u64 v[6:7], s[10:11], 0, v[6:7]
	v_lshl_add_u64 v[6:7], v[6:7], 0, v[2:3]
	v_mul_f32_e32 v5, 0x3c800000, v46
	global_store_dwordx2 v[6:7], v[8:9], off
	v_mul_f32_e32 v6, 0xbfb8aa3b, v5
	v_exp_f32_e32 v6, v6
	v_add_u32_e32 v4, 0xb0, v4
	v_add_f32_e32 v6, 1.0, v6
	v_rcp_f32_e32 v6, v6
	s_nop 0
	v_mul_f32_e32 v5, v5, v6
	v_mul_f32_e32 v6, 0x3c800000, v47
	v_mul_f32_e32 v7, 0xbfb8aa3b, v6
	v_exp_f32_e32 v7, v7
	v_mul_f32_e32 v5, v5, v42
	v_mul_f32_e32 v5, 0x3e000000, v5
	v_med3_f32 v5, v5, s40, v189
	v_add_f32_e32 v7, 1.0, v7
	v_rcp_f32_e32 v7, v7
	s_nop 0
	v_mul_f32_e32 v6, v6, v7
	v_mul_f32_e32 v7, 0x3c800000, v48
	v_mul_f32_e32 v8, 0xbfb8aa3b, v7
	v_exp_f32_e32 v8, v8
	v_mul_f32_e32 v6, v6, v43
	v_mul_f32_e32 v6, 0x3e000000, v6
	v_add_f32_e32 v8, 1.0, v8
	v_rcp_f32_e32 v8, v8
	s_nop 0
	v_mul_f32_e32 v7, v7, v8
	v_mul_f32_e32 v8, 0x3c800000, v49
	v_mul_f32_e32 v9, 0xbfb8aa3b, v8
	v_exp_f32_e32 v9, v9
	v_mul_f32_e32 v7, v7, v44
	v_mul_f32_e32 v7, 0x3e000000, v7
	v_add_f32_e32 v9, 1.0, v9
	v_rcp_f32_e32 v9, v9
	s_nop 0
	v_mul_f32_e32 v8, v8, v9
	v_mul_f32_e32 v9, 0x3c800000, v38
	v_mul_f32_e32 v10, 0xbfb8aa3b, v9
	v_exp_f32_e32 v10, v10
	v_mul_f32_e32 v8, v8, v45
	v_mul_f32_e32 v8, 0x3e000000, v8
	v_add_f32_e32 v10, 1.0, v10
	v_rcp_f32_e32 v10, v10
	s_nop 0
	v_mul_f32_e32 v9, v9, v10
	v_mul_f32_e32 v10, 0x3c800000, v39
	v_mul_f32_e32 v11, 0xbfb8aa3b, v10
	v_exp_f32_e32 v11, v11
	v_mul_f32_e32 v9, v9, v34
	v_mul_f32_e32 v9, 0x3e000000, v9
	v_add_f32_e32 v11, 1.0, v11
	v_rcp_f32_e32 v11, v11
	s_nop 0
	v_mul_f32_e32 v10, v10, v11
	v_mul_f32_e32 v11, 0x3c800000, v40
	v_mul_f32_e32 v12, 0xbfb8aa3b, v11
	v_exp_f32_e32 v12, v12
	v_mul_f32_e32 v10, v10, v35
	v_mul_f32_e32 v10, 0x3e000000, v10
	v_add_f32_e32 v12, 1.0, v12
	v_rcp_f32_e32 v12, v12
	s_nop 0
	v_mul_f32_e32 v11, v11, v12
	v_mul_f32_e32 v12, 0x3c800000, v41
	v_mul_f32_e32 v13, 0xbfb8aa3b, v12
	v_exp_f32_e32 v13, v13
	v_mul_f32_e32 v11, v11, v36
	v_mul_f32_e32 v11, 0x3e000000, v11
	v_add_f32_e32 v13, 1.0, v13
	v_rcp_f32_e32 v13, v13
	s_nop 0
	v_mul_f32_e32 v12, v12, v13
	v_med3_f32 v13, v6, s40, v189
	v_mov_b32_e32 v6, v163
	v_cvt_pk_fp8_f32 v6, v5, v13
	v_med3_f32 v5, v7, s40, v189
	v_med3_f32 v7, v8, s40, v189
	v_med3_f32 v8, v10, s40, v189
	v_cvt_pk_fp8_f32 v6, v5, v7 op_sel:[0,0,1]
	v_med3_f32 v5, v9, s40, v189
	v_mov_b32_e32 v7, v163
	v_cvt_pk_fp8_f32 v7, v5, v8
	v_mul_f32_e32 v12, v12, v37
	v_mul_f32_e32 v12, 0x3e000000, v12
	v_med3_f32 v5, v11, s40, v189
	v_med3_f32 v8, v12, s40, v189
	v_cvt_pk_fp8_f32 v7, v5, v8 op_sel:[0,0,1]
	v_ashrrev_i32_e32 v5, 31, v4
	v_lshlrev_b64 v[4:5], 7, v[4:5]
	v_lshl_add_u64 v[4:5], s[10:11], 0, v[4:5]
	v_lshl_add_u64 v[2:3], v[4:5], 0, v[2:3]
	global_store_dwordx2 v[2:3], v[6:7], off
	s_cbranch_vccz .LBB0_2738
	s_waitcnt vmcnt(0)
	s_cmpk_gt_u32 s42, 0xff
	s_cbranch_scc1 .LBB0_2684
	s_barrier
	s_branch .LBB0_2684

.LBB0_2816:
	ds_read_b128 v[2:5], v168
	ds_read_b128 v[6:9], v168 offset:1024
	ds_read_b128 v[10:13], v168 offset:2048
	ds_read_b128 v[14:17], v168 offset:3072
	s_add_u32 s0, s26, 0x4000
	s_addc_u32 s1, s27, 0
	s_cmp_eq_u32 s53, 4
	s_cselect_b32 s34, s49, s0
	s_cselect_b32 s35, s19, s1
	s_cselect_b32 s28, s50, s51
	s_cselect_b32 s29, s17, s52
	s_add_u32 s30, s34, 0x8000
	s_addc_u32 s31, s35, 0
	v_lshl_add_u64 v[162:163], s[26:27], 0, v[156:157]
	s_add_i32 m0, s25, 0xc000
	ds_read_b128 v[174:177], v169
	ds_read_b128 v[178:181], v169 offset:1024
	ds_read_b128 v[182:185], v169 offset:2048
	ds_read_b128 v[186:189], v169 offset:3072
	ds_read_b128 v[190:193], v169 offset:4096
	ds_read_b128 v[194:197], v169 offset:5120
	ds_read_b128 v[198:201], v169 offset:6144
	ds_read_b128 v[202:205], v169 offset:7168
	global_load_lds_dwordx4 v[162:163], off
	v_lshl_add_u64 v[162:163], s[26:27], 0, v[154:155]
	s_add_i32 m0, s25, 0xe000
	s_nop 0
	global_load_lds_dwordx4 v[162:163], off
	s_waitcnt lgkmcnt(8)
	s_waitcnt vmcnt(10)
	s_barrier
	s_waitcnt lgkmcnt(0)
	s_waitcnt lgkmcnt(0)
	v_mfma_scale_f32_16x16x128_f8f6f4 v[142:145], v[2:9], v[174:181], v[142:145], v170, v170 op_sel_hi:[0,0,0]
	v_mfma_scale_f32_16x16x128_f8f6f4 v[138:141], v[10:17], v[174:181], v[138:141], v170, v170 op_sel_hi:[0,0,0]
	v_mfma_scale_f32_16x16x128_f8f6f4 v[126:129], v[2:9], v[182:189], v[126:129], v170, v170 op_sel_hi:[0,0,0]
	v_mfma_scale_f32_16x16x128_f8f6f4 v[122:125], v[10:17], v[182:189], v[122:125], v170, v170 op_sel_hi:[0,0,0]
	v_mfma_scale_f32_16x16x128_f8f6f4 v[110:113], v[2:9], v[190:197], v[110:113], v170, v170 op_sel_hi:[0,0,0]
	v_mfma_scale_f32_16x16x128_f8f6f4 v[106:109], v[10:17], v[190:197], v[106:109], v170, v170 op_sel_hi:[0,0,0]
	v_mfma_scale_f32_16x16x128_f8f6f4 v[94:97], v[2:9], v[198:205], v[94:97], v170, v170 op_sel_hi:[0,0,0]
	v_mfma_scale_f32_16x16x128_f8f6f4 v[90:93], v[10:17], v[198:205], v[90:93], v170, v170 op_sel_hi:[0,0,0]
	s_barrier
	s_add_i32 s0, s45, s37
	v_lshl_add_u64 v[162:163], s[28:29], 0, v[150:151]
	s_mov_b32 m0, s0
	ds_read_b128 v[206:209], v171
	ds_read_b128 v[210:213], v171 offset:1024
	ds_read_b128 v[214:217], v171 offset:2048
	ds_read_b128 v[218:221], v171 offset:3072
	global_load_lds_dwordx4 v[162:163], off
	v_lshl_add_u64 v[164:165], s[28:29], 0, v[146:147]
	s_add_i32 m0, s0, 0x2000
	s_nop 0
	global_load_lds_dwordx4 v[164:165], off
	s_waitcnt vmcnt(10)
	s_barrier
	s_waitcnt lgkmcnt(0)
	s_waitcnt lgkmcnt(0)
	v_mfma_scale_f32_16x16x128_f8f6f4 v[134:137], v[206:213], v[174:181], v[134:137], v170, v170 op_sel_hi:[0,0,0]
	v_mfma_scale_f32_16x16x128_f8f6f4 v[130:133], v[214:221], v[174:181], v[130:133], v170, v170 op_sel_hi:[0,0,0]
	v_mfma_scale_f32_16x16x128_f8f6f4 v[118:121], v[206:213], v[182:189], v[118:121], v170, v170 op_sel_hi:[0,0,0]
	v_mfma_scale_f32_16x16x128_f8f6f4 v[114:117], v[214:221], v[182:189], v[114:117], v170, v170 op_sel_hi:[0,0,0]
	v_mfma_scale_f32_16x16x128_f8f6f4 v[102:105], v[206:213], v[190:197], v[102:105], v170, v170 op_sel_hi:[0,0,0]
	v_mfma_scale_f32_16x16x128_f8f6f4 v[98:101], v[214:221], v[190:197], v[98:101], v170, v170 op_sel_hi:[0,0,0]
	v_mfma_scale_f32_16x16x128_f8f6f4 v[86:89], v[206:213], v[198:205], v[86:89], v170, v170 op_sel_hi:[0,0,0]
	v_mfma_scale_f32_16x16x128_f8f6f4 v[82:85], v[214:221], v[198:205], v[82:85], v170, v170 op_sel_hi:[0,0,0]
	s_mov_b32 m0, s25
	v_lshl_add_u64 v[222:223], s[34:35], 0, v[152:153]
	s_barrier
	ds_read_b128 v[174:177], v169 offset:16384
	ds_read_b128 v[178:181], v169 offset:17408
	ds_read_b128 v[182:185], v169 offset:18432
	ds_read_b128 v[186:189], v169 offset:19456
	ds_read_b128 v[190:193], v169 offset:20480
	ds_read_b128 v[194:197], v169 offset:21504
	ds_read_b128 v[198:201], v169 offset:22528
	ds_read_b128 v[202:205], v169 offset:23552
	global_load_lds_dwordx4 v[222:223], off
	v_lshl_add_u64 v[222:223], s[34:35], 0, v[148:149]
	s_mov_b32 m0, s38
	s_nop 0
	global_load_lds_dwordx4 v[222:223], off
	s_waitcnt vmcnt(10)
	s_barrier
	s_waitcnt lgkmcnt(0)
	s_waitcnt lgkmcnt(0)
	v_mfma_scale_f32_16x16x128_f8f6f4 v[78:81], v[2:9], v[174:181], v[78:81], v170, v170 op_sel_hi:[0,0,0]
	v_mfma_scale_f32_16x16x128_f8f6f4 v[74:77], v[10:17], v[174:181], v[74:77], v170, v170 op_sel_hi:[0,0,0]
	v_mfma_scale_f32_16x16x128_f8f6f4 v[62:65], v[2:9], v[182:189], v[62:65], v170, v170 op_sel_hi:[0,0,0]
	v_mfma_scale_f32_16x16x128_f8f6f4 v[58:61], v[10:17], v[182:189], v[58:61], v170, v170 op_sel_hi:[0,0,0]
	v_mfma_scale_f32_16x16x128_f8f6f4 v[46:49], v[2:9], v[190:197], v[46:49], v170, v170 op_sel_hi:[0,0,0]
	v_mfma_scale_f32_16x16x128_f8f6f4 v[42:45], v[10:17], v[190:197], v[42:45], v170, v170 op_sel_hi:[0,0,0]
	v_mfma_scale_f32_16x16x128_f8f6f4 v[30:33], v[2:9], v[198:205], v[30:33], v170, v170 op_sel_hi:[0,0,0]
	v_mfma_scale_f32_16x16x128_f8f6f4 v[26:29], v[10:17], v[198:205], v[26:29], v170, v170 op_sel_hi:[0,0,0]
	s_barrier
	s_add_u32 s0, s28, 0x20000
	s_addc_u32 s1, s29, 0
	s_add_i32 s54, s46, s37
	v_lshl_add_u64 v[2:3], s[0:1], 0, v[150:151]
	s_mov_b32 m0, s54
	s_nop 0
	global_load_lds_dwordx4 v[2:3], off
	v_lshl_add_u64 v[2:3], s[0:1], 0, v[146:147]
	s_add_i32 m0, s54, 0x2000
	s_nop 0
	global_load_lds_dwordx4 v[2:3], off
	s_waitcnt vmcnt(10)
	s_barrier
	v_mfma_scale_f32_16x16x128_f8f6f4 v[70:73], v[206:213], v[174:181], v[70:73], v170, v170 op_sel_hi:[0,0,0]
	v_mfma_scale_f32_16x16x128_f8f6f4 v[66:69], v[214:221], v[174:181], v[66:69], v170, v170 op_sel_hi:[0,0,0]
	v_mfma_scale_f32_16x16x128_f8f6f4 v[54:57], v[206:213], v[182:189], v[54:57], v170, v170 op_sel_hi:[0,0,0]
	v_mfma_scale_f32_16x16x128_f8f6f4 v[50:53], v[214:221], v[182:189], v[50:53], v170, v170 op_sel_hi:[0,0,0]
	v_mfma_scale_f32_16x16x128_f8f6f4 v[38:41], v[206:213], v[190:197], v[38:41], v170, v170 op_sel_hi:[0,0,0]
	v_mfma_scale_f32_16x16x128_f8f6f4 v[34:37], v[214:221], v[190:197], v[34:37], v170, v170 op_sel_hi:[0,0,0]
	v_mfma_scale_f32_16x16x128_f8f6f4 v[22:25], v[206:213], v[198:205], v[22:25], v170, v170 op_sel_hi:[0,0,0]
	v_mfma_scale_f32_16x16x128_f8f6f4 v[18:21], v[214:221], v[198:205], v[18:21], v170, v170 op_sel_hi:[0,0,0]
	s_add_i32 s54, 0, 0x18000
	v_add_u32_e32 v14, s54, v167
	s_barrier
	ds_read_b128 v[2:5], v14
	ds_read_b128 v[6:9], v14 offset:1024
	ds_read_b128 v[10:13], v14 offset:2048
	ds_read_b128 v[14:17], v14 offset:3072
	s_add_u32 s0, s34, 0x4000
	s_addc_u32 s1, s35, 0
	s_mov_b32 m0, s39
	v_lshl_add_u64 v[206:207], s[0:1], 0, v[152:153]
	ds_read_b128 v[174:177], v169 offset:32768
	ds_read_b128 v[178:181], v169 offset:33792
	ds_read_b128 v[182:185], v169 offset:34816
	ds_read_b128 v[186:189], v169 offset:35840
	ds_read_b128 v[190:193], v169 offset:36864
	ds_read_b128 v[194:197], v169 offset:37888
	ds_read_b128 v[198:201], v169 offset:38912
	ds_read_b128 v[202:205], v169 offset:39936
	global_load_lds_dwordx4 v[206:207], off
	v_lshl_add_u64 v[206:207], s[0:1], 0, v[148:149]
	s_mov_b32 m0, s40
	s_nop 0
	global_load_lds_dwordx4 v[206:207], off
	s_waitcnt lgkmcnt(8)
	s_waitcnt vmcnt(10)
	s_barrier
	s_waitcnt lgkmcnt(0)
	s_waitcnt lgkmcnt(0)
	v_mfma_scale_f32_16x16x128_f8f6f4 v[142:145], v[2:9], v[174:181], v[142:145], v170, v170 op_sel_hi:[0,0,0]
	v_mfma_scale_f32_16x16x128_f8f6f4 v[138:141], v[10:17], v[174:181], v[138:141], v170, v170 op_sel_hi:[0,0,0]
	v_mfma_scale_f32_16x16x128_f8f6f4 v[126:129], v[2:9], v[182:189], v[126:129], v170, v170 op_sel_hi:[0,0,0]
	v_mfma_scale_f32_16x16x128_f8f6f4 v[122:125], v[10:17], v[182:189], v[122:125], v170, v170 op_sel_hi:[0,0,0]
	v_mfma_scale_f32_16x16x128_f8f6f4 v[110:113], v[2:9], v[190:197], v[110:113], v170, v170 op_sel_hi:[0,0,0]
	v_mfma_scale_f32_16x16x128_f8f6f4 v[106:109], v[10:17], v[190:197], v[106:109], v170, v170 op_sel_hi:[0,0,0]
	v_mfma_scale_f32_16x16x128_f8f6f4 v[94:97], v[2:9], v[198:205], v[94:97], v170, v170 op_sel_hi:[0,0,0]
	v_mfma_scale_f32_16x16x128_f8f6f4 v[90:93], v[10:17], v[198:205], v[90:93], v170, v170 op_sel_hi:[0,0,0]
	s_barrier
	s_add_i32 s34, 0, 0x1c000
	s_add_i32 s0, s54, s37
	v_add_u32_e32 v173, s34, v167
	v_lshl_add_u64 v[162:163], v[162:163], 0, s[12:13]
	s_mov_b32 m0, s0
	ds_read_b128 v[206:209], v173
	ds_read_b128 v[210:213], v173 offset:1024
	ds_read_b128 v[214:217], v173 offset:2048
	ds_read_b128 v[218:221], v173 offset:3072
	global_load_lds_dwordx4 v[162:163], off
	v_lshl_add_u64 v[162:163], v[164:165], 0, s[12:13]
	s_add_i32 m0, s0, 0x2000
	s_nop 0
	global_load_lds_dwordx4 v[162:163], off
	s_waitcnt vmcnt(10)
	s_barrier
	s_waitcnt lgkmcnt(0)
	s_waitcnt lgkmcnt(0)
	v_mfma_scale_f32_16x16x128_f8f6f4 v[134:137], v[206:213], v[174:181], v[134:137], v170, v170 op_sel_hi:[0,0,0]
	v_mfma_scale_f32_16x16x128_f8f6f4 v[130:133], v[214:221], v[174:181], v[130:133], v170, v170 op_sel_hi:[0,0,0]
	v_mfma_scale_f32_16x16x128_f8f6f4 v[118:121], v[206:213], v[182:189], v[118:121], v170, v170 op_sel_hi:[0,0,0]
	v_mfma_scale_f32_16x16x128_f8f6f4 v[114:117], v[214:221], v[182:189], v[114:117], v170, v170 op_sel_hi:[0,0,0]
	v_mfma_scale_f32_16x16x128_f8f6f4 v[102:105], v[206:213], v[190:197], v[102:105], v170, v170 op_sel_hi:[0,0,0]
	v_mfma_scale_f32_16x16x128_f8f6f4 v[98:101], v[214:221], v[190:197], v[98:101], v170, v170 op_sel_hi:[0,0,0]
	v_mfma_scale_f32_16x16x128_f8f6f4 v[86:89], v[206:213], v[198:205], v[86:89], v170, v170 op_sel_hi:[0,0,0]
	v_mfma_scale_f32_16x16x128_f8f6f4 v[82:85], v[214:221], v[198:205], v[82:85], v170, v170 op_sel_hi:[0,0,0]
	s_mov_b32 m0, s43
	v_lshl_add_u64 v[162:163], s[30:31], 0, v[152:153]
	s_barrier
	ds_read_b128 v[174:177], v169 offset:49152
	ds_read_b128 v[178:181], v169 offset:50176
	ds_read_b128 v[182:185], v169 offset:51200
	ds_read_b128 v[186:189], v169 offset:52224
	ds_read_b128 v[190:193], v169 offset:53248
	ds_read_b128 v[194:197], v169 offset:54272
	ds_read_b128 v[198:201], v169 offset:55296
	ds_read_b128 v[202:205], v169 offset:56320
	global_load_lds_dwordx4 v[162:163], off
	v_lshl_add_u64 v[162:163], s[30:31], 0, v[148:149]
	s_mov_b32 m0, s44
	s_nop 0
	global_load_lds_dwordx4 v[162:163], off
	s_waitcnt vmcnt(10)
	s_barrier
	s_waitcnt lgkmcnt(0)
	s_waitcnt lgkmcnt(0)
	v_mfma_scale_f32_16x16x128_f8f6f4 v[78:81], v[2:9], v[174:181], v[78:81], v170, v170 op_sel_hi:[0,0,0]
	v_mfma_scale_f32_16x16x128_f8f6f4 v[74:77], v[10:17], v[174:181], v[74:77], v170, v170 op_sel_hi:[0,0,0]
	v_mfma_scale_f32_16x16x128_f8f6f4 v[62:65], v[2:9], v[182:189], v[62:65], v170, v170 op_sel_hi:[0,0,0]
	v_mfma_scale_f32_16x16x128_f8f6f4 v[58:61], v[10:17], v[182:189], v[58:61], v170, v170 op_sel_hi:[0,0,0]
	v_mfma_scale_f32_16x16x128_f8f6f4 v[46:49], v[2:9], v[190:197], v[46:49], v170, v170 op_sel_hi:[0,0,0]
	v_mfma_scale_f32_16x16x128_f8f6f4 v[42:45], v[10:17], v[190:197], v[42:45], v170, v170 op_sel_hi:[0,0,0]
	v_mfma_scale_f32_16x16x128_f8f6f4 v[30:33], v[2:9], v[198:205], v[30:33], v170, v170 op_sel_hi:[0,0,0]
	v_mfma_scale_f32_16x16x128_f8f6f4 v[26:29], v[10:17], v[198:205], v[26:29], v170, v170 op_sel_hi:[0,0,0]
	s_barrier
	s_add_u32 s0, s28, 0x20080
	s_addc_u32 s1, s29, 0
	s_add_i32 s28, s34, s37
	v_lshl_add_u64 v[2:3], s[0:1], 0, v[150:151]
	s_mov_b32 m0, s28
	s_nop 0
	global_load_lds_dwordx4 v[2:3], off
	v_lshl_add_u64 v[2:3], s[0:1], 0, v[146:147]
	s_add_i32 m0, s28, 0x2000
	s_nop 0
	global_load_lds_dwordx4 v[2:3], off
	s_waitcnt vmcnt(10)
	s_barrier
	v_mfma_scale_f32_16x16x128_f8f6f4 v[70:73], v[206:213], v[174:181], v[70:73], v170, v170 op_sel_hi:[0,0,0]
	v_mfma_scale_f32_16x16x128_f8f6f4 v[66:69], v[214:221], v[174:181], v[66:69], v170, v170 op_sel_hi:[0,0,0]
	v_mfma_scale_f32_16x16x128_f8f6f4 v[54:57], v[206:213], v[182:189], v[54:57], v170, v170 op_sel_hi:[0,0,0]
	v_mfma_scale_f32_16x16x128_f8f6f4 v[50:53], v[214:221], v[182:189], v[50:53], v170, v170 op_sel_hi:[0,0,0]
	v_mfma_scale_f32_16x16x128_f8f6f4 v[38:41], v[206:213], v[190:197], v[38:41], v170, v170 op_sel_hi:[0,0,0]
	v_mfma_scale_f32_16x16x128_f8f6f4 v[34:37], v[214:221], v[190:197], v[34:37], v170, v170 op_sel_hi:[0,0,0]
	v_mfma_scale_f32_16x16x128_f8f6f4 v[22:25], v[206:213], v[198:205], v[22:25], v170, v170 op_sel_hi:[0,0,0]
	v_mfma_scale_f32_16x16x128_f8f6f4 v[18:21], v[214:221], v[198:205], v[18:21], v170, v170 op_sel_hi:[0,0,0]
	s_add_i32 s53, s53, 2
	s_add_u32 s51, s51, 0x100
	s_addc_u32 s52, s52, 0
	s_add_u32 s26, s26, 0x10000
	s_addc_u32 s27, s27, 0
	s_cmp_gt_u32 s53, 5
	s_barrier
	s_cbranch_scc0 .LBB0_2816
	v_pk_mul_f32 v[8:9], v[142:143], s[14:15] op_sel_hi:[1,0]
	v_pk_mul_f32 v[6:7], v[144:145], s[14:15] op_sel_hi:[1,0]
	v_med3_f32 v14, v8, s47, v172
	v_med3_f32 v9, v9, s47, v172
	v_mov_b32_e32 v8, 0
	v_cvt_pk_fp8_f32 v8, v14, v9
	v_pk_mul_f32 v[12:13], v[138:139], s[14:15] op_sel_hi:[1,0]
	v_pk_mul_f32 v[10:11], v[140:141], s[14:15] op_sel_hi:[1,0]
	v_med3_f32 v6, v6, s47, v172
	v_med3_f32 v7, v7, s47, v172
	v_med3_f32 v12, v12, s47, v172
	v_med3_f32 v13, v13, s47, v172
	v_mov_b32_e32 v9, 0
	v_mov_b32_e32 v3, v1
	v_mov_b32_e32 v2, v166
	s_lshl_b32 s0, s48, 8
	v_cvt_pk_fp8_f32 v9, v12, v13
	v_cvt_pk_fp8_f32 v8, v6, v7 op_sel:[0,0,1]
	v_med3_f32 v6, v10, s47, v172
	v_med3_f32 v7, v11, s47, v172
	v_pk_mul_f32 v[10:11], v[134:135], s[14:15] op_sel_hi:[1,0]
	s_nop 15
	s_nop 15
	s_or_b32 s0, s0, s42
	v_pk_mul_f32 v[14:15], v[130:131], s[14:15] op_sel_hi:[1,0]
	v_med3_f32 v17, v10, s47, v172
	v_med3_f32 v11, v11, s47, v172
	v_mov_b32_e32 v10, 0
	v_lshl_add_u32 v2, v2, 3, s0
	s_lshl_b32 s0, s24, 8
	v_cvt_pk_fp8_f32 v10, v17, v11
	v_med3_f32 v14, v14, s47, v172
	v_med3_f32 v15, v15, s47, v172
	v_mov_b32_e32 v11, 0
	s_add_i32 s0, s0, s15
	v_cvt_pk_fp8_f32 v11, v14, v15
	v_add_u32_e32 v16, s0, v3
	v_cvt_pk_fp8_f32 v9, v6, v7 op_sel:[0,0,1]
	v_pk_mul_f32 v[6:7], v[136:137], s[14:15] op_sel_hi:[1,0]
	v_mov_b32_e32 v4, v16
	v_pk_mul_f32 v[12:13], v[132:133], s[14:15] op_sel_hi:[1,0]
	v_med3_f32 v6, v6, s47, v172
	v_med3_f32 v7, v7, s47, v172
	v_cvt_pk_fp8_f32 v10, v6, v7 op_sel:[0,0,1]
	v_ashrrev_i32_e32 v5, 31, v4
	v_med3_f32 v6, v12, s47, v172
	v_med3_f32 v7, v13, s47, v172
	v_lshlrev_b64 v[4:5], 10, v[4:5]
	v_cvt_pk_fp8_f32 v11, v6, v7 op_sel:[0,0,1]
	v_ashrrev_i32_e32 v3, 31, v2
	v_lshl_add_u64 v[4:5], s[10:11], 0, v[4:5]
	v_lshl_add_u64 v[4:5], v[4:5], 0, v[2:3]
	global_store_dwordx2 v[4:5], v[8:9], off
	global_store_dwordx2 v[4:5], v[10:11], off offset:128
	v_pk_mul_f32 v[8:9], v[126:127], s[14:15] op_sel_hi:[1,0]
	v_pk_mul_f32 v[6:7], v[128:129], s[14:15] op_sel_hi:[1,0]
	v_med3_f32 v14, v8, s47, v172
	v_med3_f32 v9, v9, s47, v172
	v_mov_b32_e32 v8, 0
	v_cvt_pk_fp8_f32 v8, v14, v9
	v_pk_mul_f32 v[12:13], v[122:123], s[14:15] op_sel_hi:[1,0]
	v_pk_mul_f32 v[10:11], v[124:125], s[14:15] op_sel_hi:[1,0]
	v_med3_f32 v6, v6, s47, v172
	v_med3_f32 v7, v7, s47, v172
	v_med3_f32 v12, v12, s47, v172
	v_med3_f32 v13, v13, s47, v172
	v_mov_b32_e32 v9, 0
	v_cvt_pk_fp8_f32 v9, v12, v13
	v_cvt_pk_fp8_f32 v8, v6, v7 op_sel:[0,0,1]
	v_med3_f32 v6, v10, s47, v172
	v_med3_f32 v7, v11, s47, v172
	v_pk_mul_f32 v[10:11], v[118:119], s[14:15] op_sel_hi:[1,0]
	v_pk_mul_f32 v[14:15], v[114:115], s[14:15] op_sel_hi:[1,0]
	v_med3_f32 v17, v10, s47, v172
	v_med3_f32 v11, v11, s47, v172
	v_mov_b32_e32 v10, 0
	v_cvt_pk_fp8_f32 v10, v17, v11
	v_med3_f32 v14, v14, s47, v172
	v_med3_f32 v15, v15, s47, v172
	v_mov_b32_e32 v11, 0
	v_cvt_pk_fp8_f32 v11, v14, v15
	v_cvt_pk_fp8_f32 v9, v6, v7 op_sel:[0,0,1]
	v_pk_mul_f32 v[6:7], v[120:121], s[14:15] op_sel_hi:[1,0]
	v_add_u32_e32 v4, 16, v16
	v_pk_mul_f32 v[12:13], v[116:117], s[14:15] op_sel_hi:[1,0]
	v_med3_f32 v6, v6, s47, v172
	v_med3_f32 v7, v7, s47, v172
	v_cvt_pk_fp8_f32 v10, v6, v7 op_sel:[0,0,1]
	v_ashrrev_i32_e32 v5, 31, v4
	v_med3_f32 v6, v12, s47, v172
	v_med3_f32 v7, v13, s47, v172
	v_lshlrev_b64 v[4:5], 10, v[4:5]
	v_cvt_pk_fp8_f32 v11, v6, v7 op_sel:[0,0,1]
	v_lshl_add_u64 v[4:5], s[10:11], 0, v[4:5]
	v_lshl_add_u64 v[4:5], v[4:5], 0, v[2:3]
	global_store_dwordx2 v[4:5], v[8:9], off
	global_store_dwordx2 v[4:5], v[10:11], off offset:128
	v_pk_mul_f32 v[8:9], v[110:111], s[14:15] op_sel_hi:[1,0]
	v_pk_mul_f32 v[6:7], v[112:113], s[14:15] op_sel_hi:[1,0]
	v_med3_f32 v14, v8, s47, v172
	v_med3_f32 v9, v9, s47, v172
	v_mov_b32_e32 v8, 0
	v_cvt_pk_fp8_f32 v8, v14, v9
	v_pk_mul_f32 v[12:13], v[106:107], s[14:15] op_sel_hi:[1,0]
	v_pk_mul_f32 v[10:11], v[108:109], s[14:15] op_sel_hi:[1,0]
	v_med3_f32 v6, v6, s47, v172
	v_med3_f32 v7, v7, s47, v172
	v_med3_f32 v12, v12, s47, v172
	v_med3_f32 v13, v13, s47, v172
	v_mov_b32_e32 v9, 0
	v_cvt_pk_fp8_f32 v9, v12, v13
	v_cvt_pk_fp8_f32 v8, v6, v7 op_sel:[0,0,1]
	v_med3_f32 v6, v10, s47, v172
	v_med3_f32 v7, v11, s47, v172
	v_pk_mul_f32 v[10:11], v[102:103], s[14:15] op_sel_hi:[1,0]
	v_pk_mul_f32 v[14:15], v[98:99], s[14:15] op_sel_hi:[1,0]
	v_med3_f32 v17, v10, s47, v172
	v_med3_f32 v11, v11, s47, v172
	v_mov_b32_e32 v10, 0
	v_cvt_pk_fp8_f32 v10, v17, v11
	v_med3_f32 v14, v14, s47, v172
	v_med3_f32 v15, v15, s47, v172
	v_mov_b32_e32 v11, 0
	v_cvt_pk_fp8_f32 v11, v14, v15
	v_cvt_pk_fp8_f32 v9, v6, v7 op_sel:[0,0,1]
	v_pk_mul_f32 v[6:7], v[104:105], s[14:15] op_sel_hi:[1,0]
	v_add_u32_e32 v4, 32, v16
	v_pk_mul_f32 v[12:13], v[100:101], s[14:15] op_sel_hi:[1,0]
	v_med3_f32 v6, v6, s47, v172
	v_med3_f32 v7, v7, s47, v172
	v_cvt_pk_fp8_f32 v10, v6, v7 op_sel:[0,0,1]
	v_ashrrev_i32_e32 v5, 31, v4
	v_med3_f32 v6, v12, s47, v172
	v_med3_f32 v7, v13, s47, v172
	v_lshlrev_b64 v[4:5], 10, v[4:5]
	v_cvt_pk_fp8_f32 v11, v6, v7 op_sel:[0,0,1]
	v_lshl_add_u64 v[4:5], s[10:11], 0, v[4:5]
	v_lshl_add_u64 v[4:5], v[4:5], 0, v[2:3]
	global_store_dwordx2 v[4:5], v[8:9], off
	global_store_dwordx2 v[4:5], v[10:11], off offset:128
	v_pk_mul_f32 v[8:9], v[94:95], s[14:15] op_sel_hi:[1,0]
	v_pk_mul_f32 v[6:7], v[96:97], s[14:15] op_sel_hi:[1,0]
	v_med3_f32 v14, v8, s47, v172
	v_med3_f32 v9, v9, s47, v172
	v_mov_b32_e32 v8, 0
	v_cvt_pk_fp8_f32 v8, v14, v9
	v_pk_mul_f32 v[12:13], v[90:91], s[14:15] op_sel_hi:[1,0]
	v_pk_mul_f32 v[10:11], v[92:93], s[14:15] op_sel_hi:[1,0]
	v_med3_f32 v6, v6, s47, v172
	v_med3_f32 v7, v7, s47, v172
	v_med3_f32 v12, v12, s47, v172
	v_med3_f32 v13, v13, s47, v172
	v_mov_b32_e32 v9, 0
	v_cvt_pk_fp8_f32 v9, v12, v13
	v_cvt_pk_fp8_f32 v8, v6, v7 op_sel:[0,0,1]
	v_med3_f32 v6, v10, s47, v172
	v_med3_f32 v7, v11, s47, v172
	v_pk_mul_f32 v[10:11], v[86:87], s[14:15] op_sel_hi:[1,0]
	v_pk_mul_f32 v[14:15], v[82:83], s[14:15] op_sel_hi:[1,0]
	v_med3_f32 v17, v10, s47, v172
	v_med3_f32 v11, v11, s47, v172
	v_mov_b32_e32 v10, 0
	v_cvt_pk_fp8_f32 v10, v17, v11
	v_med3_f32 v14, v14, s47, v172
	v_med3_f32 v15, v15, s47, v172
	v_mov_b32_e32 v11, 0
	v_cvt_pk_fp8_f32 v11, v14, v15
	v_cvt_pk_fp8_f32 v9, v6, v7 op_sel:[0,0,1]
	v_pk_mul_f32 v[6:7], v[88:89], s[14:15] op_sel_hi:[1,0]
	v_add_u32_e32 v4, 48, v16
	v_pk_mul_f32 v[12:13], v[84:85], s[14:15] op_sel_hi:[1,0]
	v_med3_f32 v6, v6, s47, v172
	v_med3_f32 v7, v7, s47, v172
	v_cvt_pk_fp8_f32 v10, v6, v7 op_sel:[0,0,1]
	v_ashrrev_i32_e32 v5, 31, v4
	v_med3_f32 v6, v12, s47, v172
	v_med3_f32 v7, v13, s47, v172
	v_lshlrev_b64 v[4:5], 10, v[4:5]
	v_cvt_pk_fp8_f32 v11, v6, v7 op_sel:[0,0,1]
	v_lshl_add_u64 v[4:5], s[10:11], 0, v[4:5]
	v_lshl_add_u64 v[4:5], v[4:5], 0, v[2:3]
	global_store_dwordx2 v[4:5], v[8:9], off
	global_store_dwordx2 v[4:5], v[10:11], off offset:128
	v_pk_mul_f32 v[8:9], v[78:79], s[14:15] op_sel_hi:[1,0]
	v_pk_mul_f32 v[6:7], v[80:81], s[14:15] op_sel_hi:[1,0]
	v_med3_f32 v14, v8, s47, v172
	v_med3_f32 v9, v9, s47, v172
	v_mov_b32_e32 v8, 0
	v_cvt_pk_fp8_f32 v8, v14, v9
	v_pk_mul_f32 v[12:13], v[74:75], s[14:15] op_sel_hi:[1,0]
	v_pk_mul_f32 v[10:11], v[76:77], s[14:15] op_sel_hi:[1,0]
	v_med3_f32 v6, v6, s47, v172
	v_med3_f32 v7, v7, s47, v172
	v_med3_f32 v12, v12, s47, v172
	v_med3_f32 v13, v13, s47, v172
	v_mov_b32_e32 v9, 0
	v_cvt_pk_fp8_f32 v9, v12, v13
	v_cvt_pk_fp8_f32 v8, v6, v7 op_sel:[0,0,1]
	v_med3_f32 v6, v10, s47, v172
	v_med3_f32 v7, v11, s47, v172
	v_pk_mul_f32 v[10:11], v[70:71], s[14:15] op_sel_hi:[1,0]
	v_pk_mul_f32 v[14:15], v[66:67], s[14:15] op_sel_hi:[1,0]
	v_med3_f32 v17, v10, s47, v172
	v_med3_f32 v11, v11, s47, v172
	v_mov_b32_e32 v10, 0
	v_cvt_pk_fp8_f32 v10, v17, v11
	v_med3_f32 v14, v14, s47, v172
	v_med3_f32 v15, v15, s47, v172
	v_mov_b32_e32 v11, 0
	v_cvt_pk_fp8_f32 v11, v14, v15
	v_cvt_pk_fp8_f32 v9, v6, v7 op_sel:[0,0,1]
	v_pk_mul_f32 v[6:7], v[72:73], s[14:15] op_sel_hi:[1,0]
	v_add_u32_e32 v4, 0x80, v16
	v_pk_mul_f32 v[12:13], v[68:69], s[14:15] op_sel_hi:[1,0]
	v_med3_f32 v6, v6, s47, v172
	v_med3_f32 v7, v7, s47, v172
	v_cvt_pk_fp8_f32 v10, v6, v7 op_sel:[0,0,1]
	v_ashrrev_i32_e32 v5, 31, v4
	v_med3_f32 v6, v12, s47, v172
	v_med3_f32 v7, v13, s47, v172
	v_lshlrev_b64 v[4:5], 10, v[4:5]
	v_cvt_pk_fp8_f32 v11, v6, v7 op_sel:[0,0,1]
	v_lshl_add_u64 v[4:5], s[10:11], 0, v[4:5]
	v_lshl_add_u64 v[4:5], v[4:5], 0, v[2:3]
	global_store_dwordx2 v[4:5], v[8:9], off
	global_store_dwordx2 v[4:5], v[10:11], off offset:128
	v_pk_mul_f32 v[8:9], v[62:63], s[14:15] op_sel_hi:[1,0]
	v_pk_mul_f32 v[6:7], v[64:65], s[14:15] op_sel_hi:[1,0]
	v_med3_f32 v14, v8, s47, v172
	v_med3_f32 v9, v9, s47, v172
	v_mov_b32_e32 v8, 0
	v_cvt_pk_fp8_f32 v8, v14, v9
	v_pk_mul_f32 v[12:13], v[58:59], s[14:15] op_sel_hi:[1,0]
	v_pk_mul_f32 v[10:11], v[60:61], s[14:15] op_sel_hi:[1,0]
	v_med3_f32 v6, v6, s47, v172
	v_med3_f32 v7, v7, s47, v172
	v_med3_f32 v12, v12, s47, v172
	v_med3_f32 v13, v13, s47, v172
	v_mov_b32_e32 v9, 0
	v_cvt_pk_fp8_f32 v9, v12, v13
	v_cvt_pk_fp8_f32 v8, v6, v7 op_sel:[0,0,1]
	v_med3_f32 v6, v10, s47, v172
	v_med3_f32 v7, v11, s47, v172
	v_pk_mul_f32 v[10:11], v[54:55], s[14:15] op_sel_hi:[1,0]
	v_pk_mul_f32 v[14:15], v[50:51], s[14:15] op_sel_hi:[1,0]
	v_med3_f32 v17, v10, s47, v172
	v_med3_f32 v11, v11, s47, v172
	v_mov_b32_e32 v10, 0
	v_cvt_pk_fp8_f32 v10, v17, v11
	v_med3_f32 v14, v14, s47, v172
	v_med3_f32 v15, v15, s47, v172
	v_mov_b32_e32 v11, 0
	v_cvt_pk_fp8_f32 v11, v14, v15
	v_cvt_pk_fp8_f32 v9, v6, v7 op_sel:[0,0,1]
	v_pk_mul_f32 v[6:7], v[56:57], s[14:15] op_sel_hi:[1,0]
	v_add_u32_e32 v4, 0x90, v16
	v_pk_mul_f32 v[12:13], v[52:53], s[14:15] op_sel_hi:[1,0]
	v_med3_f32 v6, v6, s47, v172
	v_med3_f32 v7, v7, s47, v172
	v_cvt_pk_fp8_f32 v10, v6, v7 op_sel:[0,0,1]
	v_ashrrev_i32_e32 v5, 31, v4
	v_med3_f32 v6, v12, s47, v172
	v_med3_f32 v7, v13, s47, v172
	v_lshlrev_b64 v[4:5], 10, v[4:5]
	v_cvt_pk_fp8_f32 v11, v6, v7 op_sel:[0,0,1]
	v_lshl_add_u64 v[4:5], s[10:11], 0, v[4:5]
	v_lshl_add_u64 v[4:5], v[4:5], 0, v[2:3]
	global_store_dwordx2 v[4:5], v[8:9], off
	global_store_dwordx2 v[4:5], v[10:11], off offset:128
	v_pk_mul_f32 v[8:9], v[46:47], s[14:15] op_sel_hi:[1,0]
	v_pk_mul_f32 v[6:7], v[48:49], s[14:15] op_sel_hi:[1,0]
	v_med3_f32 v14, v8, s47, v172
	v_med3_f32 v9, v9, s47, v172
	v_mov_b32_e32 v8, 0
	v_cvt_pk_fp8_f32 v8, v14, v9
	v_pk_mul_f32 v[12:13], v[42:43], s[14:15] op_sel_hi:[1,0]
	v_pk_mul_f32 v[10:11], v[44:45], s[14:15] op_sel_hi:[1,0]
	v_med3_f32 v6, v6, s47, v172
	v_med3_f32 v7, v7, s47, v172
	v_med3_f32 v12, v12, s47, v172
	v_med3_f32 v13, v13, s47, v172
	v_mov_b32_e32 v9, 0
	v_cvt_pk_fp8_f32 v9, v12, v13
	v_cvt_pk_fp8_f32 v8, v6, v7 op_sel:[0,0,1]
	v_med3_f32 v6, v10, s47, v172
	v_med3_f32 v7, v11, s47, v172
	v_pk_mul_f32 v[10:11], v[38:39], s[14:15] op_sel_hi:[1,0]
	v_pk_mul_f32 v[14:15], v[34:35], s[14:15] op_sel_hi:[1,0]
	v_med3_f32 v17, v10, s47, v172
	v_med3_f32 v11, v11, s47, v172
	v_mov_b32_e32 v10, 0
	v_cvt_pk_fp8_f32 v10, v17, v11
	v_med3_f32 v14, v14, s47, v172
	v_med3_f32 v15, v15, s47, v172
	v_mov_b32_e32 v11, 0
	v_cvt_pk_fp8_f32 v11, v14, v15
	v_cvt_pk_fp8_f32 v9, v6, v7 op_sel:[0,0,1]
	v_pk_mul_f32 v[6:7], v[40:41], s[14:15] op_sel_hi:[1,0]
	v_add_u32_e32 v4, 0xa0, v16
	v_pk_mul_f32 v[12:13], v[36:37], s[14:15] op_sel_hi:[1,0]
	v_med3_f32 v6, v6, s47, v172
	v_med3_f32 v7, v7, s47, v172
	v_cvt_pk_fp8_f32 v10, v6, v7 op_sel:[0,0,1]
	v_ashrrev_i32_e32 v5, 31, v4
	v_med3_f32 v6, v12, s47, v172
	v_med3_f32 v7, v13, s47, v172
	v_lshlrev_b64 v[4:5], 10, v[4:5]
	v_cvt_pk_fp8_f32 v11, v6, v7 op_sel:[0,0,1]
	v_lshl_add_u64 v[4:5], s[10:11], 0, v[4:5]
	v_lshl_add_u64 v[4:5], v[4:5], 0, v[2:3]
	global_store_dwordx2 v[4:5], v[8:9], off
	global_store_dwordx2 v[4:5], v[10:11], off offset:128
	v_pk_mul_f32 v[8:9], v[30:31], s[14:15] op_sel_hi:[1,0]
	v_pk_mul_f32 v[6:7], v[32:33], s[14:15] op_sel_hi:[1,0]
	v_med3_f32 v14, v8, s47, v172
	v_med3_f32 v9, v9, s47, v172
	v_mov_b32_e32 v8, 0
	v_cvt_pk_fp8_f32 v8, v14, v9
	v_pk_mul_f32 v[12:13], v[26:27], s[14:15] op_sel_hi:[1,0]
	v_pk_mul_f32 v[10:11], v[28:29], s[14:15] op_sel_hi:[1,0]
	v_med3_f32 v6, v6, s47, v172
	v_med3_f32 v7, v7, s47, v172
	v_med3_f32 v12, v12, s47, v172
	v_med3_f32 v13, v13, s47, v172
	v_mov_b32_e32 v9, 0
	v_cvt_pk_fp8_f32 v9, v12, v13
	v_cvt_pk_fp8_f32 v8, v6, v7 op_sel:[0,0,1]
	v_med3_f32 v6, v10, s47, v172
	v_med3_f32 v7, v11, s47, v172
	v_pk_mul_f32 v[10:11], v[22:23], s[14:15] op_sel_hi:[1,0]
	v_add_u32_e32 v4, 0xb0, v16
	v_pk_mul_f32 v[14:15], v[18:19], s[14:15] op_sel_hi:[1,0]
	v_med3_f32 v16, v10, s47, v172
	v_med3_f32 v11, v11, s47, v172
	v_mov_b32_e32 v10, 0
	v_cvt_pk_fp8_f32 v10, v16, v11
	v_med3_f32 v14, v14, s47, v172
	v_med3_f32 v15, v15, s47, v172
	v_mov_b32_e32 v11, 0
	v_cvt_pk_fp8_f32 v11, v14, v15
	v_cvt_pk_fp8_f32 v9, v6, v7 op_sel:[0,0,1]
	v_pk_mul_f32 v[6:7], v[24:25], s[14:15] op_sel_hi:[1,0]
	v_pk_mul_f32 v[12:13], v[20:21], s[14:15] op_sel_hi:[1,0]
	v_med3_f32 v6, v6, s47, v172
	v_med3_f32 v7, v7, s47, v172
	v_cvt_pk_fp8_f32 v10, v6, v7 op_sel:[0,0,1]
	v_ashrrev_i32_e32 v5, 31, v4
	v_med3_f32 v6, v12, s47, v172
	v_med3_f32 v7, v13, s47, v172
	v_lshlrev_b64 v[4:5], 10, v[4:5]
	v_cvt_pk_fp8_f32 v11, v6, v7 op_sel:[0,0,1]
	v_lshl_add_u64 v[4:5], s[10:11], 0, v[4:5]
	v_lshl_add_u64 v[2:3], v[4:5], 0, v[2:3]
	s_and_b64 vcc, exec, s[6:7]
	s_mov_b32 s48, s16
	s_mov_b32 s24, s18
	s_mov_b64 s[26:27], s[22:23]
	s_mov_b64 s[28:29], s[20:21]
	global_store_dwordx2 v[2:3], v[8:9], off
	global_store_dwordx2 v[2:3], v[10:11], off offset:128
	s_cbranch_vccz .LBB0_2809
	s_waitcnt vmcnt(0)
	s_cmpk_gt_u32 s4, 0xff
	s_cbranch_scc1 .LBB0_2820
	s_barrier

.LBB0_2874:
	s_or_b64 exec, exec, s[2:3]
	s_waitcnt lgkmcnt(0)
	s_barrier
	s_load_dwordx8 s[12:19], s[84:85], 0xf0
	v_mov_b32_e32 v33, 0
	v_and_b32_e32 v44, 63, v0
	v_lshlrev_b32_e32 v32, 4, v44
	s_waitcnt lgkmcnt(0)
	s_mov_b32 s8, s18
	s_add_u32 s4, s8, 0x3e00000
	s_addc_u32 s5, s19, 0
	v_lshl_add_u64 v[0:1], s[12:13], 0, v[32:33]
	s_mov_b64 s[0:1], 0x7000
	v_lshl_add_u64 v[4:5], s[14:15], 0, v[32:33]
	v_lshl_add_u64 v[34:35], v[0:1], 0, s[0:1]
	v_lshl_add_u64 v[36:37], v[4:5], 0, s[0:1]
	s_movk_i32 s0, 0x7000
	s_add_u32 s6, s8, 0x3900000
	v_add_co_u32_e32 v0, vcc, s0, v0
	s_addc_u32 s7, s19, 0
	s_nop 0
	v_addc_co_u32_e32 v1, vcc, 0, v1, vcc
	s_add_u32 s10, s8, 0xa100000
	v_add_co_u32_e32 v38, vcc, s0, v4
	s_addc_u32 s11, s19, 0
	v_readlane_b32 s0, v253, 36
	v_readlane_b32 s1, v253, 37
	s_add_u32 s0, s10, s0
	s_addc_u32 s1, s11, s1
	v_readlane_b32 s12, v253, 38
	s_mov_b32 s2, s16
	v_addc_co_u32_e32 v39, vcc, 0, v5, vcc
	v_readlane_b32 s13, v253, 39
	s_add_u32 s12, s10, s12
	v_lshlrev_b32_e32 v32, 3, v44
	global_load_dwordx4 v[0:3], v[0:1], off
	s_nop 0
	global_load_dwordx4 v[4:7], v[38:39], off
	global_load_dwordx4 v[8:11], v[34:35], off offset:1024
	global_load_dwordx4 v[12:15], v[34:35], off offset:2048
	global_load_dwordx4 v[16:19], v[36:37], off offset:1024
	global_load_dwordx4 v[20:23], v[36:37], off offset:2048
	global_load_dwordx4 v[24:27], v[34:35], off offset:3072
	global_load_dwordx4 v[28:31], v[36:37], off offset:3072
	s_addc_u32 s13, s11, s13
	v_lshl_add_u64 v[38:39], s[0:1], 0, v[32:33]
	v_lshl_add_u64 v[46:47], s[12:13], 0, v[32:33]
	global_load_dwordx2 v[64:65], v[38:39], off
	global_load_dwordx2 v[62:63], v[38:39], off offset:512
	global_load_dwordx2 v[60:61], v[38:39], off offset:1024
	global_load_dwordx2 v[58:59], v[38:39], off offset:1536
	global_load_dwordx2 v[42:43], v[46:47], off
	global_load_dwordx2 v[40:41], v[46:47], off offset:512
	global_load_dwordx2 v[36:37], v[46:47], off offset:1024
	global_load_dwordx2 v[34:35], v[46:47], off offset:1536
	s_mov_b32 s14, s19
	v_cmp_gt_u32_e64 s[0:1], 16, v44
	v_mov_b32_e32 v39, -1
	v_lshlrev_b32_e32 v38, 11, v44
	v_mov_b32_e32 v80, v33
	v_mov_b32_e32 v79, -1
	s_and_saveexec_b64 s[12:13], s[0:1]
	s_cbranch_execz .LBB0_2876
	v_readlane_b32 s18, v253, 34
	s_ashr_i32 s20, s68, 11
	v_readlane_b32 s19, v253, 35
	s_mov_b32 s16, s18
	s_ashr_i32 s18, s18, 11
	s_ashr_i32 s21, s20, 31
	s_ashr_i32 s19, s18, 31
	s_lshl_b64 s[20:21], s[20:21], 15
	s_and_b32 s9, s68, 0x7ff
	s_lshl_b64 s[18:19], s[18:19], 15
	s_and_b32 s3, s16, 0x7ff
	s_or_b32 s9, s20, s9
	s_or_b32 s3, s18, s3
	v_or_b32_e32 v46, s9, v38
	v_mov_b32_e32 v47, s21
	v_lshl_add_u64 v[48:49], v[46:47], 1, s[4:5]
	v_or_b32_e32 v50, s3, v38
	v_mov_b32_e32 v51, s19
	v_lshl_add_u64 v[46:47], v[46:47], 2, s[6:7]
	v_lshl_add_u64 v[52:53], v[50:51], 1, s[4:5]
	v_lshl_add_u64 v[50:51], v[50:51], 2, s[6:7]
	global_load_sshort v79, v[48:49], off
	global_load_dword v80, v[46:47], off
	global_load_sshort v39, v[52:53], off
	global_load_dword v33, v[50:51], off

.LBB0_2878:
	v_mov_b32_e32 v80, v71
	v_mov_b32_e32 v81, v68
	v_mov_b32_e32 v82, v70
	v_mov_b32_e32 v83, v69
	v_pk_add_f32 v[80:81], v[80:81], v[82:83]
	v_mov_b32_e32 v82, v67
	v_mov_b32_e32 v83, v62
	v_mov_b32_e32 v84, v66
	v_mov_b32_e32 v85, v63
	v_pk_add_f32 v[82:83], v[82:83], v[84:85]
	v_add_f32_e32 v32, v80, v81
	v_pk_add_f32 v[82:83], v[82:83], v[82:83] op_sel_hi:[0,1]
	v_add_f32_e32 v81, 0, v32
	v_add_f32_e32 v85, v64, v65
	v_add_f32_e32 v87, v60, v61
	v_mov_b32_e32 v84, v58
	v_mov_b32_e32 v86, v59
	v_mov_b32_e32 v82, v72
	v_mov_b32_e32 v80, v73
	v_pk_add_f32 v[84:85], v[84:85], v[86:87]
	v_pk_add_f32 v[80:81], v[82:83], v[80:81]
	s_ashr_i32 s69, s68, 31
	v_pk_add_f32 v[80:81], v[84:85], v[80:81]
	s_nop 0
	v_add_f32_e32 v32, v80, v81
	s_nop 1
	v_add_f32_dpp v32, v32, v32 quad_perm:[1,0,3,2] row_mask:0xf bank_mask:0xf bound_ctrl:1
	s_nop 1
	v_add_f32_dpp v32, v32, v32 quad_perm:[2,3,0,1] row_mask:0xf bank_mask:0xf bound_ctrl:1
	s_nop 1
	v_add_f32_dpp v32, v32, v32 row_half_mirror row_mask:0xf bank_mask:0xf bound_ctrl:1
	s_nop 1
	v_add_f32_dpp v32, v32, v32 row_mirror row_mask:0xf bank_mask:0xf bound_ctrl:1
	s_nop 0
	v_readlane_b32 s11, v32, 16
	v_readlane_b32 s12, v32, 48
	v_readlane_b32 s2, v32, 0
	v_readlane_b32 s3, v32, 32
	v_mov_b32_e32 v80, s11
	v_mov_b32_e32 v81, s12
	v_pk_add_f32 v[80:81], s[2:3], v[80:81]
	s_nop 0
	v_add_f32_e32 v79, v80, v81
	v_fmac_f32_e32 v71, 0xba800000, v79
	v_fmac_f32_e32 v70, 0xba800000, v79
	v_fmac_f32_e32 v69, 0xba800000, v79
	v_fmac_f32_e32 v68, 0xba800000, v79
	v_pk_mul_f32 v[80:81], v[68:69], v[68:69]
	v_pk_mul_f32 v[82:83], v[70:71], v[70:71]
	v_fmac_f32_e32 v67, 0xba800000, v79
	v_pk_mov_b32 v[84:85], v[82:83], v[80:81] op_sel:[1,0]
	v_mov_b32_e32 v83, v81
	v_fmac_f32_e32 v66, 0xba800000, v79
	v_fmac_f32_e32 v63, 0xba800000, v79
	v_fmac_f32_e32 v62, 0xba800000, v79
	v_pk_add_f32 v[80:81], v[84:85], v[82:83]
	v_pk_mul_f32 v[82:83], v[62:63], v[62:63]
	v_pk_mul_f32 v[84:85], v[66:67], v[66:67]
	v_fmac_f32_e32 v64, 0xba800000, v79
	v_pk_mov_b32 v[86:87], v[84:85], v[82:83] op_sel:[1,0]
	v_mov_b32_e32 v85, v83
	v_fmac_f32_e32 v65, 0xba800000, v79
	v_fmac_f32_e32 v60, 0xba800000, v79
	v_mul_f32_e32 v32, v64, v64
	v_pk_add_f32 v[82:83], v[86:87], v[84:85]
	v_fmac_f32_e32 v61, 0xba800000, v79
	v_pk_fma_f32 v[84:85], v[64:65], v[64:65], v[32:33] op_sel_hi:[1,1,0]
	v_mul_f32_e32 v32, v60, v60
	v_pk_add_f32 v[80:81], v[80:81], v[80:81] op_sel_hi:[0,1]
	v_pk_add_f32 v[82:83], v[82:83], v[82:83] op_sel_hi:[0,1]
	v_pk_fma_f32 v[86:87], v[60:61], v[60:61], v[32:33] op_sel_hi:[1,1,0]
	v_fmamk_f32 v73, v79, 0xba800000, v73
	v_fmamk_f32 v72, v79, 0xba800000, v72
	v_fmamk_f32 v59, v79, 0xba800000, v59
	v_fmac_f32_e32 v58, 0xba800000, v79
	v_mul_f32_e32 v84, v58, v58
	v_mul_f32_e32 v86, v59, v59
	v_mul_f32_e32 v80, v72, v72
	v_mul_f32_e32 v82, v73, v73
	v_pk_add_f32 v[84:85], v[84:85], v[86:87]
	v_pk_add_f32 v[80:81], v[80:81], v[82:83]
	s_nop 0
	v_pk_add_f32 v[80:81], v[84:85], v[80:81]
	s_nop 0
	v_add_f32_e32 v32, v80, v81
	s_nop 1
	v_add_f32_dpp v32, v32, v32 quad_perm:[1,0,3,2] row_mask:0xf bank_mask:0xf bound_ctrl:1
	s_nop 1
	v_add_f32_dpp v32, v32, v32 quad_perm:[2,3,0,1] row_mask:0xf bank_mask:0xf bound_ctrl:1
	s_nop 1
	v_add_f32_dpp v32, v32, v32 row_half_mirror row_mask:0xf bank_mask:0xf bound_ctrl:1
	s_nop 1
	v_add_f32_dpp v32, v32, v32 row_mirror row_mask:0xf bank_mask:0xf bound_ctrl:1
	s_nop 0
	v_readlane_b32 s11, v32, 16
	v_readlane_b32 s12, v32, 48
	v_readlane_b32 s2, v32, 0
	v_readlane_b32 s3, v32, 32
	v_mov_b32_e32 v80, s11
	v_mov_b32_e32 v81, s12
	v_pk_add_f32 v[80:81], s[2:3], v[80:81]
	s_nop 0
	v_add_f32_e32 v32, v80, v81
	v_fmamk_f32 v32, v32, 0x3a800000, v74
	v_mul_f32_e32 v79, 0x4f800000, v32
	v_cmp_gt_f32_e32 vcc, s17, v32
	s_nop 1
	v_cndmask_b32_e32 v32, v32, v79, vcc
	v_sqrt_f32_e32 v79, v32
	s_nop 0
	v_add_u32_e32 v80, -1, v79
	v_fma_f32 v81, -v80, v79, v32
	v_cmp_ge_f32_e64 s[2:3], 0, v81
	v_add_u32_e32 v81, 1, v79
	s_nop 0
	v_cndmask_b32_e64 v80, v79, v80, s[2:3]
	v_fma_f32 v79, -v81, v79, v32
	v_cmp_lt_f32_e64 s[2:3], 0, v79
	s_nop 1
	v_cndmask_b32_e64 v79, v80, v81, s[2:3]
	v_mul_f32_e32 v80, 0x37800000, v79
	v_cndmask_b32_e32 v79, v79, v80, vcc
	v_cmp_class_f32_e32 vcc, v32, v75
	s_nop 1
	v_cndmask_b32_e32 v32, v79, v32, vcc
	v_div_scale_f32 v79, s[2:3], v32, v32, 1.0
	v_rcp_f32_e32 v80, v79
	s_lshl_b64 s[2:3], s[68:69], 12
	s_sub_i32 s68, s10, s33
	s_cmp_gt_i32 s68, 0xffff
	v_fma_f32 v81, -v79, v80, 1.0
	v_fmac_f32_e32 v80, v81, v80
	v_div_scale_f32 v81, vcc, 1.0, v32, 1.0
	v_mul_f32_e32 v82, v81, v80
	v_fma_f32 v83, -v79, v82, v81
	v_fmac_f32_e32 v82, v83, v80
	v_fma_f32 v79, -v79, v82, v81
	v_div_fmas_f32 v79, v79, v80, v82
	v_div_fixup_f32 v32, v79, v32, 1.0
	v_pk_mul_f32 v[80:81], v[70:71], v[32:33] op_sel_hi:[1,0]
	v_pk_mul_f32 v[68:69], v[68:69], v[32:33] op_sel_hi:[1,0]
	v_pk_mul_f32 v[62:63], v[62:63], v[32:33] op_sel_hi:[1,0]
	v_pk_fma_f32 v[70:71], v[2:3], v[68:69], v[6:7]
	v_pk_fma_f32 v[68:69], v[0:1], v[80:81], v[4:5]
	v_lshl_add_u64 v[80:81], v[48:49], 0, s[2:3]
	v_pk_mul_f32 v[64:65], v[64:65], v[32:33] op_sel_hi:[1,0]
	v_pk_mul_f32 v[60:61], v[60:61], v[32:33] op_sel_hi:[1,0]
	global_store_dwordx4 v[80:81], v[68:71], off nt
	v_pk_mul_f32 v[66:67], v[66:67], v[32:33] op_sel_hi:[1,0]
	v_pk_mul_f32 v[58:59], v[58:59], v[32:33] op_sel_hi:[1,0]
	v_pk_fma_f32 v[68:69], v[10:11], v[62:63], v[18:19]
	v_pk_fma_f32 v[62:63], v[14:15], v[60:61], v[22:23]
	v_pk_fma_f32 v[60:61], v[12:13], v[64:65], v[20:21]
	global_store_dwordx4 v[80:81], v[60:63], off offset:2048 nt
	v_pk_fma_f32 v[66:67], v[8:9], v[66:67], v[16:17]
	v_pk_fma_f32 v[58:59], v[24:25], v[58:59], v[28:29]
	v_pk_mul_f32 v[60:61], v[72:73], v[32:33] op_sel_hi:[1,0]
	global_store_dwordx4 v[80:81], v[66:69], off offset:1024 nt
	v_pk_fma_f32 v[60:61], v[26:27], v[60:61], v[30:31]
	global_store_dwordx4 v[80:81], v[58:61], off offset:3072 nt
	v_mov_b32_e32 v64, v42
	v_mov_b32_e32 v65, v43
	v_mov_b32_e32 v62, v40
	v_mov_b32_e32 v63, v41
	v_mov_b32_e32 v60, v36
	v_mov_b32_e32 v61, v37
	v_mov_b32_e32 v58, v34
	v_mov_b32_e32 v59, v35
	s_waitcnt vmcnt(0) lgkmcnt(0)
	v_mov_b64_e32 v[34:35], v[50:51]
	v_mov_b64_e32 v[36:37], v[52:53]
	v_mov_b64_e32 v[40:41], v[54:55]
	v_mov_b64_e32 v[42:43], v[56:57]
	v_mov_b32_e32 v79, v39
	v_mov_b32_e32 v39, v77
	v_mov_b32_e32 v80, v33
	v_mov_b32_e32 v33, v78
	s_cbranch_scc1 .LBB0_2888
.LBB0_2879:
	s_add_i32 s10, s68, s94
	s_cmp_gt_i32 s10, 0xffff
	v_mov_b32_e32 v78, v33
	s_cbranch_scc1 .LBB0_2883
	s_ashr_i32 s11, s10, 31
	s_lshl_b64 s[2:3], s[10:11], 11
	v_lshl_add_u64 v[66:67], v[46:47], 0, s[2:3]
	global_load_dwordx2 v[56:57], v[66:67], off
	global_load_dwordx2 v[54:55], v[66:67], off offset:512
	global_load_dwordx2 v[52:53], v[66:67], off offset:1024
	global_load_dwordx2 v[50:51], v[66:67], off offset:1536
	v_mov_b32_e32 v77, v39
	v_mov_b32_e32 v78, v33
	s_and_saveexec_b64 s[2:3], s[0:1]
	s_cbranch_execz .LBB0_2882
	s_ashr_i32 s12, s10, 11
	s_ashr_i32 s13, s12, 31
	s_lshl_b64 s[12:13], s[12:13], 15
	v_or_b32_e32 v32, s12, v38
	s_and_b32 s11, s10, 0x7ff
	v_mov_b32_e32 v67, s13
	v_or_b32_e32 v66, s11, v32
	v_lshl_add_u64 v[68:69], v[66:67], 1, s[4:5]
	v_lshl_add_u64 v[66:67], v[66:67], 2, s[6:7]
	global_load_sshort v77, v[68:69], off
	global_load_dword v78, v[66:67], off

.LBB0_2885:
	s_add_u32 s20, s14, -1
	s_addc_u32 s21, s15, -1
	s_lshl_b32 s13, s13, 5
	s_and_b64 vcc, s[20:21], s[14:15]
	s_add_i32 s14, s13, s11
	s_ashr_i32 s15, s14, 31
	s_ashr_i32 s13, s12, 31
	s_lshl_b64 s[14:15], s[14:15], 18
	s_lshl_b64 s[12:13], s[12:13], 10
	s_add_u32 s14, s9, s14
	s_addc_u32 s15, s16, s15
	s_add_u32 s12, s14, s12
	s_addc_u32 s13, s15, s13
	s_lshl_b32 s3, s3, 5
	s_add_i32 s14, s3, s11
	s_ashr_i32 s15, s14, 31
	s_ashr_i32 s3, s2, 31
	s_lshl_b64 s[14:15], s[14:15], 18
	s_lshl_b64 s[2:3], s[2:3], 10
	s_add_u32 s14, s9, s14
	s_addc_u32 s15, s16, s15
	s_add_u32 s2, s14, s2
	s_addc_u32 s3, s15, s3
	v_lshl_add_u64 v[82:83], s[12:13], 0, v[44:45]
	v_lshl_add_u64 v[84:85], s[2:3], 0, v[44:45]
	global_load_dword v81, v[82:83], off
	global_load_dword v90, v[82:83], off offset:256
	global_load_dword v94, v[82:83], off offset:512
	global_load_dword v98, v[84:85], off
	global_load_dword v102, v[84:85], off offset:256
	global_load_dword v106, v[84:85], off offset:512
	global_load_dword v114, v[84:85], off offset:768
	global_load_dword v110, v[82:83], off offset:768
	v_mul_f32_e32 v82, s18, v76
	s_cmp_eq_u64 vcc, 0
	s_waitcnt vmcnt(0) lgkmcnt(0)
	v_cvt_pk_f32_fp8_e32 v[96:97], v98
	v_cvt_pk_f32_fp8_sdwa v[98:99], v98 src0_sel:WORD_1
	v_cvt_pk_f32_fp8_e32 v[100:101], v102
	v_cvt_pk_f32_fp8_sdwa v[102:103], v102 src0_sel:WORD_1
	v_cvt_pk_f32_fp8_e32 v[104:105], v106
	v_cvt_pk_f32_fp8_sdwa v[106:107], v106 src0_sel:WORD_1
	v_cvt_pk_f32_fp8_e32 v[112:113], v114
	v_cvt_pk_f32_fp8_sdwa v[114:115], v114 src0_sel:WORD_1
	v_cvt_pk_f32_fp8_e32 v[84:85], v81
	v_cvt_pk_f32_fp8_sdwa v[86:87], v81 src0_sel:WORD_1
	v_cvt_pk_f32_fp8_e32 v[88:89], v90
	v_cvt_pk_f32_fp8_sdwa v[90:91], v90 src0_sel:WORD_1
	v_cvt_pk_f32_fp8_e32 v[92:93], v94
	v_cvt_pk_f32_fp8_sdwa v[94:95], v94 src0_sel:WORD_1
	v_cvt_pk_f32_fp8_e32 v[108:109], v110
	v_cvt_pk_f32_fp8_sdwa v[110:111], v110 src0_sel:WORD_1
	v_pk_mul_f32 v[98:99], v[32:33], v[98:99] op_sel_hi:[0,1]
	v_pk_mul_f32 v[96:97], v[32:33], v[96:97] op_sel_hi:[0,1]
	v_pk_mul_f32 v[102:103], v[32:33], v[102:103] op_sel_hi:[0,1]
	v_pk_mul_f32 v[100:101], v[32:33], v[100:101] op_sel_hi:[0,1]
	v_pk_mul_f32 v[106:107], v[32:33], v[106:107] op_sel_hi:[0,1]
	v_pk_mul_f32 v[104:105], v[32:33], v[104:105] op_sel_hi:[0,1]
	v_pk_mul_f32 v[114:115], v[32:33], v[114:115] op_sel_hi:[0,1]
	v_pk_mul_f32 v[112:113], v[32:33], v[112:113] op_sel_hi:[0,1]
	v_pk_fma_f32 v[84:85], v[82:83], v[84:85], v[96:97] op_sel_hi:[0,1,1]
	v_pk_fma_f32 v[86:87], v[82:83], v[86:87], v[98:99] op_sel_hi:[0,1,1]
	v_pk_fma_f32 v[88:89], v[82:83], v[88:89], v[100:101] op_sel_hi:[0,1,1]
	v_pk_fma_f32 v[90:91], v[82:83], v[90:91], v[102:103] op_sel_hi:[0,1,1]
	v_pk_fma_f32 v[92:93], v[82:83], v[92:93], v[104:105] op_sel_hi:[0,1,1]
	v_pk_fma_f32 v[94:95], v[82:83], v[94:95], v[106:107] op_sel_hi:[0,1,1]
	v_pk_fma_f32 v[96:97], v[82:83], v[108:109], v[112:113] op_sel_hi:[0,1,1]
	v_pk_fma_f32 v[82:83], v[82:83], v[110:111], v[114:115] op_sel_hi:[0,1,1]
	v_pk_add_f32 v[68:69], v[68:69], v[86:87]
	v_pk_add_f32 v[70:71], v[70:71], v[84:85]
	v_pk_add_f32 v[62:63], v[62:63], v[90:91]
	v_pk_add_f32 v[66:67], v[66:67], v[88:89]
	v_pk_add_f32 v[60:61], v[60:61], v[94:95]
	v_pk_add_f32 v[64:65], v[64:65], v[92:93]
	v_pk_add_f32 v[72:73], v[72:73], v[82:83]
	v_pk_add_f32 v[58:59], v[58:59], v[96:97]
	s_cbranch_scc1 .LBB0_2878
